# speedup vs baseline: 1.0016x; 1.0016x over previous
.LBB0_86:
	s_ashr_i32 s37, s36, 31
	s_lshl_b64 s[36:37], s[36:37], 20
	s_add_u32 s36, s48, s36
	s_addc_u32 s37, s49, s37
	s_ashr_i32 s5, s4, 31
	v_lshlrev_b32_e32 v3, 6, v1
	s_lshl_b64 s[4:5], s[4:5], 20
	v_and_b32_e32 v2, 48, v1
	v_and_b32_e32 v4, 0x3c0, v3
	v_lshlrev_b32_e32 v1, 2, v1
	s_add_u32 s4, s46, s4
	v_or_b32_e32 v5, v4, v2
	v_and_b32_e32 v1, 32, v1
	v_lshlrev_b32_e32 v0, 13, v0
	s_mov_b32 s72, 0x18000
	s_addc_u32 s5, s47, s5
	v_and_b32_e32 v111, 0x6000, v0
	s_add_i32 s40, s1, 0x10000
	s_add_i32 s41, s1, 0x18000
	s_add_i32 s64, s1, 0x12000
	s_add_i32 s65, s1, 0x1a000
	s_add_i32 s68, s1, 0x14000
	s_add_i32 s69, s1, 0x1c000
	s_add_i32 s70, s1, 0x16000
	s_add_i32 s71, s1, 0x1e000
	v_bitop3_b32 v0, v5, s72, v1 bitop3:0xde
	s_mov_b32 s72, 0x10400
	v_bitop3_b32 v149, v5, s72, v1 bitop3:0xde
	s_add_u32 s72, s44, s2
	s_addc_u32 s73, s45, s3
	s_add_i32 s2, s74, s75
	s_ashr_i32 s3, s2, 31
	s_waitcnt vmcnt(0)
	s_lshl_b64 s[2:3], s[2:3], 20
	v_bitop3_b32 v110, v4, v1, v2 bitop3:0x36
	v_and_b32_e32 v112, 0xffffc000, v3
	s_add_u32 s74, s10, s2
	v_mov_b32_e32 v4, 0
	v_or_b32_e32 v113, 0x800, v112
	v_or_b32_e32 v114, 0x1000, v112
	v_or_b32_e32 v115, 0x1800, v112
	v_or_b32_e32 v116, 0x2000, v112
	v_or_b32_e32 v117, 0x2800, v112
	v_or_b32_e32 v118, 0x3000, v112
	v_or_b32_e32 v119, 0x3800, v112
	v_bitop3_b32 v145, v5, s33, v1 bitop3:0xde
	s_addc_u32 s75, s11, s3
	s_mov_b64 s[2:3], 0
	s_mov_b32 s76, 1
	v_add_u32_e32 v150, v0, v111
	v_mov_b32_e32 v5, v4
	v_mov_b32_e32 v6, v4
	v_mov_b32_e32 v7, v4
	v_mov_b32_e32 v72, v4
	v_mov_b32_e32 v73, v4
	v_mov_b32_e32 v74, v4
	v_mov_b32_e32 v75, v4
	v_mov_b32_e32 v12, v4
	v_mov_b32_e32 v13, v4
	v_mov_b32_e32 v14, v4
	v_mov_b32_e32 v15, v4
	v_mov_b32_e32 v76, v4
	v_mov_b32_e32 v77, v4
	v_mov_b32_e32 v78, v4
	v_mov_b32_e32 v79, v4
	v_mov_b32_e32 v16, v4
	v_mov_b32_e32 v17, v4
	v_mov_b32_e32 v18, v4
	v_mov_b32_e32 v19, v4
	v_mov_b32_e32 v80, v4
	v_mov_b32_e32 v81, v4
	v_mov_b32_e32 v82, v4
	v_mov_b32_e32 v83, v4
	v_mov_b32_e32 v20, v4
	v_mov_b32_e32 v21, v4
	v_mov_b32_e32 v22, v4
	v_mov_b32_e32 v23, v4
	v_mov_b32_e32 v84, v4
	v_mov_b32_e32 v85, v4
	v_mov_b32_e32 v86, v4
	v_mov_b32_e32 v87, v4
	v_mov_b32_e32 v24, v4
	v_mov_b32_e32 v25, v4
	v_mov_b32_e32 v26, v4
	v_mov_b32_e32 v27, v4
	v_mov_b32_e32 v88, v4
	v_mov_b32_e32 v89, v4
	v_mov_b32_e32 v90, v4
	v_mov_b32_e32 v91, v4
	v_mov_b32_e32 v28, v4
	v_mov_b32_e32 v29, v4
	v_mov_b32_e32 v30, v4
	v_mov_b32_e32 v31, v4
	v_mov_b32_e32 v92, v4
	v_mov_b32_e32 v93, v4
	v_mov_b32_e32 v94, v4
	v_mov_b32_e32 v95, v4
	v_mov_b32_e32 v32, v4
	v_mov_b32_e32 v33, v4
	v_mov_b32_e32 v34, v4
	v_mov_b32_e32 v35, v4
	v_mov_b32_e32 v96, v4
	v_mov_b32_e32 v97, v4
	v_mov_b32_e32 v98, v4
	v_mov_b32_e32 v99, v4
	v_mov_b32_e32 v36, v4
	v_mov_b32_e32 v37, v4
	v_mov_b32_e32 v38, v4
	v_mov_b32_e32 v39, v4
	v_mov_b32_e32 v100, v4
	v_mov_b32_e32 v101, v4
	v_mov_b32_e32 v102, v4
	v_mov_b32_e32 v103, v4
	v_mov_b32_e32 v40, v4
	v_mov_b32_e32 v41, v4
	v_mov_b32_e32 v42, v4
	v_mov_b32_e32 v43, v4
	v_mov_b32_e32 v120, v4
	v_mov_b32_e32 v121, v4
	v_mov_b32_e32 v122, v4
	v_mov_b32_e32 v123, v4
	v_mov_b32_e32 v44, v4
	v_mov_b32_e32 v45, v4
	v_mov_b32_e32 v46, v4
	v_mov_b32_e32 v47, v4
	v_mov_b32_e32 v124, v4
	v_mov_b32_e32 v125, v4
	v_mov_b32_e32 v126, v4
	v_mov_b32_e32 v127, v4
	v_mov_b32_e32 v48, v4
	v_mov_b32_e32 v49, v4
	v_mov_b32_e32 v50, v4
	v_mov_b32_e32 v51, v4
	v_mov_b32_e32 v128, v4
	v_mov_b32_e32 v129, v4
	v_mov_b32_e32 v130, v4
	v_mov_b32_e32 v131, v4
	v_mov_b32_e32 v52, v4
	v_mov_b32_e32 v53, v4
	v_mov_b32_e32 v54, v4
	v_mov_b32_e32 v55, v4
	v_mov_b32_e32 v132, v4
	v_mov_b32_e32 v133, v4
	v_mov_b32_e32 v134, v4
	v_mov_b32_e32 v135, v4
	v_mov_b32_e32 v56, v4
	v_mov_b32_e32 v57, v4
	v_mov_b32_e32 v58, v4
	v_mov_b32_e32 v59, v4
	v_mov_b32_e32 v136, v4
	v_mov_b32_e32 v137, v4
	v_mov_b32_e32 v138, v4
	v_mov_b32_e32 v139, v4
	v_mov_b32_e32 v60, v4
	v_mov_b32_e32 v61, v4
	v_mov_b32_e32 v62, v4
	v_mov_b32_e32 v63, v4
	v_mov_b32_e32 v140, v4
	v_mov_b32_e32 v141, v4
	v_mov_b32_e32 v142, v4
	v_mov_b32_e32 v143, v4
	v_mov_b32_e32 v64, v4
	v_mov_b32_e32 v65, v4
	v_mov_b32_e32 v66, v4
	v_mov_b32_e32 v67, v4
	v_mov_b32_e32 v0, v4
	v_mov_b32_e32 v1, v4
	v_mov_b32_e32 v2, v4
	v_mov_b32_e32 v3, v4
	v_mov_b32_e32 v68, v4
	v_mov_b32_e32 v69, v4
	v_mov_b32_e32 v70, v4
	v_mov_b32_e32 v71, v4
	v_mov_b32_e32 v8, v4
	v_mov_b32_e32 v9, v4
	v_mov_b32_e32 v10, v4
	v_mov_b32_e32 v11, v4
	s_waitcnt lgkmcnt(0)
	s_barrier
	s_add_u32 s77, s74, s2
	s_addc_u32 s82, s75, s3
	s_add_u32 s78, s77, 0x1b900080
	s_addc_u32 s79, s82, 0
	s_add_u32 s83, s72, s2
	s_addc_u32 s84, s73, s3
	s_add_u32 s80, s83, 0x3400080
	s_addc_u32 s81, s84, 0
	v_add_u32_e32 v151, v110, v111
	v_add_u32_e32 v189, v110, v112
	ds_read_b128 v[152:155], v151 offset:32768
	ds_read_b128 v[156:159], v189
	ds_read_b128 v[160:163], v151 offset:34816
	ds_read_b128 v[164:167], v189 offset:2048
	ds_read_b128 v[168:171], v151 offset:36864
	ds_read_b128 v[172:175], v151 offset:38912
	ds_read_b128 v[176:179], v189 offset:4096
	ds_read_b128 v[180:183], v189 offset:6144
	s_branch .Lmy_rot_87
.LBB0_87:
	s_add_u32 s77, s74, s2
	s_addc_u32 s82, s75, s3
	s_add_u32 s78, s77, 0x1b900080
	s_addc_u32 s79, s82, 0
	s_add_u32 s83, s72, s2
	s_addc_u32 s84, s73, s3
	s_add_u32 s80, s83, 0x3400080
	s_addc_u32 s81, s84, 0
	v_add_u32_e32 v151, v110, v111
	v_add_u32_e32 v189, v110, v112
	ds_read_b128 v[152:155], v151 offset:32768
	ds_read_b128 v[156:159], v189
	v_mfma_f32_16x16x32_bf16 v[76:79], v[160:163], v[176:179], v[76:79]
	v_mfma_f32_16x16x32_bf16 v[64:67], v[160:163], v[180:183], v[64:67]
	ds_read_b128 v[160:163], v151 offset:34816
	v_mfma_f32_16x16x32_bf16 v[12:15], v[164:167], v[176:179], v[12:15]
	v_mfma_f32_16x16x32_bf16 v[0:3], v[164:167], v[180:183], v[0:3]
	ds_read_b128 v[164:167], v189 offset:2048
	v_mfma_f32_16x16x32_bf16 v[72:75], v[168:171], v[176:179], v[72:75]
	v_mfma_f32_16x16x32_bf16 v[68:71], v[168:171], v[180:183], v[68:71]
	ds_read_b128 v[168:171], v151 offset:36864
	v_mfma_f32_16x16x32_bf16 v[4:7], v[172:175], v[176:179], v[4:7]
	v_mfma_f32_16x16x32_bf16 v[8:11], v[172:175], v[180:183], v[8:11]
	ds_read_b128 v[172:175], v151 offset:38912
	ds_read_b128 v[176:179], v189 offset:4096
	ds_read_b128 v[180:183], v189 offset:6144
.Lmy_rot_87:
	s_waitcnt lgkmcnt(6)
	v_mfma_f32_16x16x32_bf16 v[140:143], v[152:155], v[156:159], v[140:143]
	s_waitcnt lgkmcnt(5)
	v_mfma_f32_16x16x32_bf16 v[60:63], v[160:163], v[156:159], v[60:63]
	s_waitcnt lgkmcnt(4)
	s_mov_b32 m0, s40
	v_mfma_f32_16x16x32_bf16 v[132:135], v[152:155], v[164:167], v[132:135]
	global_load_lds_dwordx4 v104, s[78:79]
	v_mfma_f32_16x16x32_bf16 v[52:55], v[160:163], v[164:167], v[52:55]
	s_waitcnt lgkmcnt(3)
	v_mfma_f32_16x16x32_bf16 v[136:139], v[168:171], v[156:159], v[136:139]
	v_mfma_f32_16x16x32_bf16 v[128:131], v[168:171], v[164:167], v[128:131]
	s_waitcnt lgkmcnt(2)
	s_mov_b32 m0, s41
	v_mfma_f32_16x16x32_bf16 v[56:59], v[172:175], v[156:159], v[56:59]
	global_load_lds_dwordx4 v104, s[80:81]
	ds_read_b128 v[156:159], v189 offset:8192
	v_mfma_f32_16x16x32_bf16 v[48:51], v[172:175], v[164:167], v[48:51]
	ds_read_b128 v[164:167], v189 offset:10240
	s_waitcnt lgkmcnt(3)
	v_mfma_f32_16x16x32_bf16 v[124:127], v[152:155], v[176:179], v[124:127]
	v_mfma_f32_16x16x32_bf16 v[44:47], v[160:163], v[176:179], v[44:47]
	s_mov_b32 m0, s64
	v_mfma_f32_16x16x32_bf16 v[120:123], v[168:171], v[176:179], v[120:123]
	global_load_lds_dwordx4 v106, s[78:79]
	v_mfma_f32_16x16x32_bf16 v[40:43], v[172:175], v[176:179], v[40:43]
	ds_read_b128 v[176:179], v189 offset:12288
	s_waitcnt lgkmcnt(3)
	v_mfma_f32_16x16x32_bf16 v[100:103], v[152:155], v[180:183], v[100:103]
	v_mfma_f32_16x16x32_bf16 v[36:39], v[160:163], v[180:183], v[36:39]
	s_mov_b32 m0, s65
	v_mfma_f32_16x16x32_bf16 v[96:99], v[168:171], v[180:183], v[96:99]
	global_load_lds_dwordx4 v106, s[80:81]
	v_mfma_f32_16x16x32_bf16 v[32:35], v[172:175], v[180:183], v[32:35]
	ds_read_b128 v[180:183], v189 offset:14336
	s_waitcnt lgkmcnt(3)
	v_mfma_f32_16x16x32_bf16 v[28:31], v[160:163], v[156:159], v[28:31]
	s_waitcnt lgkmcnt(2)
	v_mfma_f32_16x16x32_bf16 v[20:23], v[160:163], v[164:167], v[20:23]
	s_waitcnt lgkmcnt(1)
	s_mov_b32 m0, s68
	v_mfma_f32_16x16x32_bf16 v[12:15], v[160:163], v[176:179], v[12:15]
	global_load_lds_dwordx4 v108, s[78:79]
	s_waitcnt lgkmcnt(0)
	v_mfma_f32_16x16x32_bf16 v[0:3], v[160:163], v[180:183], v[0:3]
	ds_read_b128 v[160:163], v151 offset:33792
	v_mfma_f32_16x16x32_bf16 v[92:95], v[152:155], v[156:159], v[92:95]
	v_mfma_f32_16x16x32_bf16 v[84:87], v[152:155], v[164:167], v[84:87]
	s_mov_b32 m0, s69
	v_mfma_f32_16x16x32_bf16 v[76:79], v[152:155], v[176:179], v[76:79]
	global_load_lds_dwordx4 v108, s[80:81]
	v_mfma_f32_16x16x32_bf16 v[64:67], v[152:155], v[180:183], v[64:67]
	ds_read_b128 v[152:155], v189 offset:1024
	v_mfma_f32_16x16x32_bf16 v[80:83], v[168:171], v[164:167], v[80:83]
	v_mfma_f32_16x16x32_bf16 v[16:19], v[172:175], v[164:167], v[16:19]
	ds_read_b128 v[164:167], v151 offset:35840
	s_mov_b32 m0, s70
	v_mfma_f32_16x16x32_bf16 v[88:91], v[168:171], v[156:159], v[88:91]
	global_load_lds_dwordx4 v146, s[78:79]
	v_mfma_f32_16x16x32_bf16 v[24:27], v[172:175], v[156:159], v[24:27]
	ds_read_b128 v[156:159], v189 offset:3072
	v_mfma_f32_16x16x32_bf16 v[72:75], v[168:171], v[176:179], v[72:75]
	v_mfma_f32_16x16x32_bf16 v[4:7], v[172:175], v[176:179], v[4:7]
	ds_read_b128 v[176:179], v189 offset:5120
	s_mov_b32 m0, s71
	v_mfma_f32_16x16x32_bf16 v[68:71], v[168:171], v[180:183], v[68:71]
	global_load_lds_dwordx4 v146, s[80:81]
	ds_read_b128 v[168:171], v151 offset:37888
	v_mfma_f32_16x16x32_bf16 v[8:11], v[172:175], v[180:183], v[8:11]
	ds_read_b128 v[172:175], v151 offset:39936
	ds_read_b128 v[180:183], v189 offset:7168
	s_waitcnt lgkmcnt(6)
	v_mfma_f32_16x16x32_bf16 v[140:143], v[160:163], v[152:155], v[140:143]
	s_waitcnt lgkmcnt(5)
	v_mfma_f32_16x16x32_bf16 v[60:63], v[164:167], v[152:155], v[60:63]
	s_waitcnt lgkmcnt(4)
	v_mfma_f32_16x16x32_bf16 v[132:135], v[160:163], v[156:159], v[132:135]
	v_mfma_f32_16x16x32_bf16 v[52:55], v[164:167], v[156:159], v[52:55]
	s_waitcnt lgkmcnt(3)
	v_mfma_f32_16x16x32_bf16 v[124:127], v[160:163], v[176:179], v[124:127]
	v_mfma_f32_16x16x32_bf16 v[44:47], v[164:167], v[176:179], v[44:47]
	s_waitcnt lgkmcnt(2)
	v_mfma_f32_16x16x32_bf16 v[136:139], v[168:171], v[152:155], v[136:139]
	s_waitcnt lgkmcnt(1)
	v_mfma_f32_16x16x32_bf16 v[56:59], v[172:175], v[152:155], v[56:59]
	ds_read_b128 v[152:155], v189 offset:9216
	v_mfma_f32_16x16x32_bf16 v[128:131], v[168:171], v[156:159], v[128:131]
	v_mfma_f32_16x16x32_bf16 v[48:51], v[172:175], v[156:159], v[48:51]
	ds_read_b128 v[156:159], v189 offset:11264
	v_mfma_f32_16x16x32_bf16 v[120:123], v[168:171], v[176:179], v[120:123]
	v_mfma_f32_16x16x32_bf16 v[40:43], v[172:175], v[176:179], v[40:43]
	ds_read_b128 v[176:179], v189 offset:13312
	s_waitcnt lgkmcnt(3)
	v_mfma_f32_16x16x32_bf16 v[100:103], v[160:163], v[180:183], v[100:103]
	v_mfma_f32_16x16x32_bf16 v[36:39], v[164:167], v[180:183], v[36:39]
	v_mfma_f32_16x16x32_bf16 v[96:99], v[168:171], v[180:183], v[96:99]
	v_mfma_f32_16x16x32_bf16 v[32:35], v[172:175], v[180:183], v[32:35]
	ds_read_b128 v[180:183], v189 offset:15360
	s_waitcnt lgkmcnt(3)
	v_mfma_f32_16x16x32_bf16 v[92:95], v[160:163], v[152:155], v[92:95]
	v_mfma_f32_16x16x32_bf16 v[28:31], v[164:167], v[152:155], v[28:31]
	v_mfma_f32_16x16x32_bf16 v[88:91], v[168:171], v[152:155], v[88:91]
	v_mfma_f32_16x16x32_bf16 v[24:27], v[172:175], v[152:155], v[24:27]
	s_waitcnt lgkmcnt(2)
	v_mfma_f32_16x16x32_bf16 v[84:87], v[160:163], v[156:159], v[84:87]
	v_mfma_f32_16x16x32_bf16 v[20:23], v[164:167], v[156:159], v[20:23]
	v_mfma_f32_16x16x32_bf16 v[80:83], v[168:171], v[156:159], v[80:83]
	v_mfma_f32_16x16x32_bf16 v[16:19], v[172:175], v[156:159], v[16:19]
	s_add_u32 s77, s77, 0x1b900100
	s_addc_u32 s78, s82, 0
	s_add_u32 s80, s83, 0x3400100
	s_addc_u32 s81, s84, 0
	s_cmp_lt_u32 s76, 31
	s_cselect_b32 s79, s78, s37
	s_cselect_b32 s78, s77, s36
	s_waitcnt vmcnt(0)
	s_waitcnt lgkmcnt(0)
	s_barrier
	s_cselect_b32 s81, s81, s5
	s_cselect_b32 s80, s80, s4
	ds_read_b128 v[152:155], v150
	v_add_u32_e32 v151, v145, v112
	ds_read_b128 v[156:159], v151
	v_mfma_f32_16x16x32_bf16 v[76:79], v[160:163], v[176:179], v[76:79]
	v_mfma_f32_16x16x32_bf16 v[64:67], v[160:163], v[180:183], v[64:67]
	ds_read_b128 v[160:163], v150 offset:2048
	v_mfma_f32_16x16x32_bf16 v[12:15], v[164:167], v[176:179], v[12:15]
	v_mfma_f32_16x16x32_bf16 v[0:3], v[164:167], v[180:183], v[0:3]
	v_add_u32_e32 v151, v145, v113
	ds_read_b128 v[164:167], v151
	v_mfma_f32_16x16x32_bf16 v[72:75], v[168:171], v[176:179], v[72:75]
	v_mfma_f32_16x16x32_bf16 v[68:71], v[168:171], v[180:183], v[68:71]
	ds_read_b128 v[168:171], v150 offset:4096
	v_mfma_f32_16x16x32_bf16 v[4:7], v[172:175], v[176:179], v[4:7]
	v_mfma_f32_16x16x32_bf16 v[8:11], v[172:175], v[180:183], v[8:11]
	ds_read_b128 v[172:175], v150 offset:6144
	v_add_u32_e32 v151, v145, v114
	ds_read_b128 v[176:179], v151
	v_add_u32_e32 v151, v145, v115
	ds_read_b128 v[180:183], v151
	s_waitcnt lgkmcnt(6)
	v_mfma_f32_16x16x32_bf16 v[140:143], v[152:155], v[156:159], v[140:143]
	s_waitcnt lgkmcnt(5)
	v_mfma_f32_16x16x32_bf16 v[60:63], v[160:163], v[156:159], v[60:63]
	s_waitcnt lgkmcnt(4)
	s_mov_b32 m0, s1
	v_mfma_f32_16x16x32_bf16 v[132:135], v[152:155], v[164:167], v[132:135]
	global_load_lds_dwordx4 v104, s[78:79]
	v_mfma_f32_16x16x32_bf16 v[52:55], v[160:163], v[164:167], v[52:55]
	s_waitcnt lgkmcnt(3)
	v_mfma_f32_16x16x32_bf16 v[136:139], v[168:171], v[156:159], v[136:139]
	v_mfma_f32_16x16x32_bf16 v[128:131], v[168:171], v[164:167], v[128:131]
	s_waitcnt lgkmcnt(2)
	s_mov_b32 m0, s39
	v_mfma_f32_16x16x32_bf16 v[56:59], v[172:175], v[156:159], v[56:59]
	global_load_lds_dwordx4 v104, s[80:81]
	v_add_u32_e32 v151, v145, v116
	ds_read_b128 v[156:159], v151
	v_mfma_f32_16x16x32_bf16 v[48:51], v[172:175], v[164:167], v[48:51]
	v_add_u32_e32 v151, v145, v117
	ds_read_b128 v[164:167], v151
	s_waitcnt lgkmcnt(3)
	v_mfma_f32_16x16x32_bf16 v[124:127], v[152:155], v[176:179], v[124:127]
	v_mfma_f32_16x16x32_bf16 v[44:47], v[160:163], v[176:179], v[44:47]
	s_mov_b32 m0, s53
	v_mfma_f32_16x16x32_bf16 v[120:123], v[168:171], v[176:179], v[120:123]
	global_load_lds_dwordx4 v106, s[78:79]
	v_mfma_f32_16x16x32_bf16 v[40:43], v[172:175], v[176:179], v[40:43]
	v_add_u32_e32 v151, v145, v118
	ds_read_b128 v[176:179], v151
	s_waitcnt lgkmcnt(3)
	v_mfma_f32_16x16x32_bf16 v[100:103], v[152:155], v[180:183], v[100:103]
	v_mfma_f32_16x16x32_bf16 v[36:39], v[160:163], v[180:183], v[36:39]
	s_mov_b32 m0, s54
	v_mfma_f32_16x16x32_bf16 v[96:99], v[168:171], v[180:183], v[96:99]
	global_load_lds_dwordx4 v106, s[80:81]
	v_mfma_f32_16x16x32_bf16 v[32:35], v[172:175], v[180:183], v[32:35]
	v_add_u32_e32 v151, v145, v119
	ds_read_b128 v[180:183], v151
	s_waitcnt lgkmcnt(3)
	v_mfma_f32_16x16x32_bf16 v[28:31], v[160:163], v[156:159], v[28:31]
	s_waitcnt lgkmcnt(2)
	v_mfma_f32_16x16x32_bf16 v[20:23], v[160:163], v[164:167], v[20:23]
	s_waitcnt lgkmcnt(1)
	s_mov_b32 m0, s55
	v_mfma_f32_16x16x32_bf16 v[12:15], v[160:163], v[176:179], v[12:15]
	global_load_lds_dwordx4 v108, s[78:79]
	s_waitcnt lgkmcnt(0)
	v_mfma_f32_16x16x32_bf16 v[0:3], v[160:163], v[180:183], v[0:3]
	ds_read_b128 v[160:163], v150 offset:1024
	v_mfma_f32_16x16x32_bf16 v[92:95], v[152:155], v[156:159], v[92:95]
	v_mfma_f32_16x16x32_bf16 v[84:87], v[152:155], v[164:167], v[84:87]
	s_mov_b32 m0, s58
	v_mfma_f32_16x16x32_bf16 v[76:79], v[152:155], v[176:179], v[76:79]
	global_load_lds_dwordx4 v108, s[80:81]
	v_mfma_f32_16x16x32_bf16 v[64:67], v[152:155], v[180:183], v[64:67]
	v_add_u32_e32 v151, v149, v112
	ds_read_b128 v[152:155], v151
	v_mfma_f32_16x16x32_bf16 v[80:83], v[168:171], v[164:167], v[80:83]
	v_mfma_f32_16x16x32_bf16 v[16:19], v[172:175], v[164:167], v[16:19]
	ds_read_b128 v[164:167], v150 offset:3072
	s_mov_b32 m0, s62
	v_mfma_f32_16x16x32_bf16 v[88:91], v[168:171], v[156:159], v[88:91]
	global_load_lds_dwordx4 v146, s[78:79]
	v_mfma_f32_16x16x32_bf16 v[24:27], v[172:175], v[156:159], v[24:27]
	v_add_u32_e32 v151, v149, v113
	ds_read_b128 v[156:159], v151
	v_mfma_f32_16x16x32_bf16 v[72:75], v[168:171], v[176:179], v[72:75]
	v_mfma_f32_16x16x32_bf16 v[4:7], v[172:175], v[176:179], v[4:7]
	v_add_u32_e32 v151, v149, v114
	ds_read_b128 v[176:179], v151
	s_mov_b32 m0, s63
	v_mfma_f32_16x16x32_bf16 v[68:71], v[168:171], v[180:183], v[68:71]
	global_load_lds_dwordx4 v146, s[80:81]
	ds_read_b128 v[168:171], v150 offset:5120
	v_mfma_f32_16x16x32_bf16 v[8:11], v[172:175], v[180:183], v[8:11]
	ds_read_b128 v[172:175], v150 offset:7168
	v_add_u32_e32 v151, v149, v115
	ds_read_b128 v[180:183], v151
	s_waitcnt lgkmcnt(6)
	v_mfma_f32_16x16x32_bf16 v[140:143], v[160:163], v[152:155], v[140:143]
	s_waitcnt lgkmcnt(5)
	v_mfma_f32_16x16x32_bf16 v[60:63], v[164:167], v[152:155], v[60:63]
	s_waitcnt lgkmcnt(4)
	v_mfma_f32_16x16x32_bf16 v[132:135], v[160:163], v[156:159], v[132:135]
	v_mfma_f32_16x16x32_bf16 v[52:55], v[164:167], v[156:159], v[52:55]
	s_waitcnt lgkmcnt(3)
	v_mfma_f32_16x16x32_bf16 v[124:127], v[160:163], v[176:179], v[124:127]
	v_mfma_f32_16x16x32_bf16 v[44:47], v[164:167], v[176:179], v[44:47]
	s_waitcnt lgkmcnt(2)
	v_mfma_f32_16x16x32_bf16 v[136:139], v[168:171], v[152:155], v[136:139]
	s_waitcnt lgkmcnt(1)
	v_mfma_f32_16x16x32_bf16 v[56:59], v[172:175], v[152:155], v[56:59]
	v_add_u32_e32 v151, v149, v116
	ds_read_b128 v[152:155], v151
	v_mfma_f32_16x16x32_bf16 v[128:131], v[168:171], v[156:159], v[128:131]
	v_mfma_f32_16x16x32_bf16 v[48:51], v[172:175], v[156:159], v[48:51]
	v_add_u32_e32 v151, v149, v117
	ds_read_b128 v[156:159], v151
	v_mfma_f32_16x16x32_bf16 v[120:123], v[168:171], v[176:179], v[120:123]
	v_mfma_f32_16x16x32_bf16 v[40:43], v[172:175], v[176:179], v[40:43]
	v_add_u32_e32 v151, v149, v118
	ds_read_b128 v[176:179], v151
	s_waitcnt lgkmcnt(3)
	v_mfma_f32_16x16x32_bf16 v[100:103], v[160:163], v[180:183], v[100:103]
	v_mfma_f32_16x16x32_bf16 v[36:39], v[164:167], v[180:183], v[36:39]
	v_mfma_f32_16x16x32_bf16 v[96:99], v[168:171], v[180:183], v[96:99]
	v_mfma_f32_16x16x32_bf16 v[32:35], v[172:175], v[180:183], v[32:35]
	v_add_u32_e32 v151, v149, v119
	ds_read_b128 v[180:183], v151
	s_waitcnt lgkmcnt(3)
	v_mfma_f32_16x16x32_bf16 v[92:95], v[160:163], v[152:155], v[92:95]
	v_mfma_f32_16x16x32_bf16 v[28:31], v[164:167], v[152:155], v[28:31]
	v_mfma_f32_16x16x32_bf16 v[88:91], v[168:171], v[152:155], v[88:91]
	v_mfma_f32_16x16x32_bf16 v[24:27], v[172:175], v[152:155], v[24:27]
	s_waitcnt lgkmcnt(2)
	v_mfma_f32_16x16x32_bf16 v[84:87], v[160:163], v[156:159], v[84:87]
	v_mfma_f32_16x16x32_bf16 v[20:23], v[164:167], v[156:159], v[20:23]
	v_mfma_f32_16x16x32_bf16 v[80:83], v[168:171], v[156:159], v[80:83]
	v_mfma_f32_16x16x32_bf16 v[16:19], v[172:175], v[156:159], v[16:19]
	s_waitcnt vmcnt(0)
	s_add_u32 s2, s2, 0x100
	s_addc_u32 s3, s3, 0
	s_add_i32 s76, s76, 2
	s_cmpk_lg_i32 s2, 0x1000
	s_waitcnt lgkmcnt(0)
	s_barrier
	s_cbranch_scc1 .LBB0_87
	v_mfma_f32_16x16x32_bf16 v[76:79], v[160:163], v[176:179], v[76:79]
	v_mfma_f32_16x16x32_bf16 v[64:67], v[160:163], v[180:183], v[64:67]
	v_mfma_f32_16x16x32_bf16 v[12:15], v[164:167], v[176:179], v[12:15]
	v_mfma_f32_16x16x32_bf16 v[0:3], v[164:167], v[180:183], v[0:3]
	v_mfma_f32_16x16x32_bf16 v[72:75], v[168:171], v[176:179], v[72:75]
	v_mfma_f32_16x16x32_bf16 v[68:71], v[168:171], v[180:183], v[68:71]
	v_mfma_f32_16x16x32_bf16 v[4:7], v[172:175], v[176:179], v[4:7]
	v_mfma_f32_16x16x32_bf16 v[8:11], v[172:175], v[180:183], v[8:11]
	s_nop 15
	s_nop 15
	v_mov_b32_e32 v145, v184
	s_movk_i32 s1, 0x100
	v_and_b32_e32 v163, 15, v145
	v_cmp_gt_u32_e64 s[2:3], s1, v145
	v_cmp_lt_u32_e32 vcc, 13, v163
	s_and_b64 s[4:5], s[2:3], vcc
	s_xor_b64 s[4:5], s[4:5], -1
	v_lshlrev_b32_e32 v149, 6, v163
	s_and_saveexec_b64 s[36:37], s[4:5]
	s_xor_b64 s[4:5], exec, s[36:37]
	v_lshlrev_b32_e32 v149, 6, v163
	s_or_saveexec_b64 s[4:5], s[4:5]
	v_bfe_u32 v150, v145, 4, 2
	v_readlane_b32 s68, v253, 18
	v_readlane_b32 s75, v253, 20
	s_xor_b64 exec, exec, s[4:5]
	s_cbranch_execz .LBB0_92
	v_mov_b32_e32 v104, 0x211c0
	v_lshl_or_b32 v104, v163, 2, v104
	ds_read_b32 v108, v104
	v_and_b32_e32 v104, 0xc0, v145
	v_lshl_add_u32 v104, v104, 2, v149
	v_lshl_or_b32 v109, v150, 4, v104
	v_add_u32_e32 v110, 0x1fc80, v109
	s_waitcnt lgkmcnt(0)
	v_pk_mul_f32 v[104:105], v[64:65], v[108:109] op_sel_hi:[1,0]
	v_pk_mul_f32 v[106:107], v[66:67], v[108:109] op_sel_hi:[1,0]
	v_add_u32_e32 v109, 0x1fd00, v109
	ds_write_b128 v110, v[104:107]
	v_pk_mul_f32 v[104:105], v[0:1], v[108:109] op_sel_hi:[1,0]
	v_pk_mul_f32 v[106:107], v[2:3], v[108:109] op_sel_hi:[1,0]
	ds_write_b128 v109, v[104:107]

.LBB0_154:
	s_ashr_i32 s21, s20, 31
	s_lshl_b64 s[20:21], s[20:21], 20
	s_add_u32 s20, s26, s20
	s_addc_u32 s21, s27, s21
	s_ashr_i32 s23, s22, 31
	s_lshl_b64 s[22:23], s[22:23], 20
	s_add_u32 s22, s8, s22
	s_addc_u32 s23, s9, s23
	s_add_u32 s44, s16, 0x80
	v_and_b32_e32 v8, 48, v7
	v_lshlrev_b32_e32 v9, 6, v7
	v_lshlrev_b32_e32 v7, 2, v7
	s_addc_u32 s45, s17, 0
	v_and_b32_e32 v10, 0x3c0, v9
	v_and_b32_e32 v149, 32, v7
	s_add_u32 s46, s18, 0x80
	v_or_b32_e32 v145, v10, v8
	v_bitop3_b32 v12, v10, v149, v8 bitop3:0x36
	s_waitcnt vmcnt(0)
	s_barrier
	v_lshlrev_b32_e32 v8, 13, v6
	s_addc_u32 s47, s19, 0
	s_add_i32 s25, s1, 0x10000
	v_lshl_add_u64 v[6:7], s[44:45], 0, v[0:1]
	s_mov_b32 s39, m0
	s_mov_b32 m0, s25
	s_nop 0
	global_load_lds_dwordx4 v[6:7], off
	s_mov_b32 m0, s39
	s_add_i32 s24, s1, 0x18000
	v_lshl_add_u64 v[6:7], s[46:47], 0, v[0:1]
	s_mov_b32 s39, m0
	s_mov_b32 m0, s24
	s_nop 0
	global_load_lds_dwordx4 v[6:7], off
	s_mov_b32 m0, s39
	v_lshl_add_u64 v[6:7], s[44:45], 0, v[2:3]
	s_add_i32 s39, s1, 0x12000
	s_mov_b32 s40, m0
	s_mov_b32 m0, s39
	s_nop 0
	global_load_lds_dwordx4 v[6:7], off
	s_mov_b32 m0, s40
	v_lshl_add_u64 v[6:7], s[46:47], 0, v[2:3]
	s_add_i32 s40, s1, 0x1a000
	s_mov_b32 s41, m0
	s_mov_b32 m0, s40
	s_nop 0
	global_load_lds_dwordx4 v[6:7], off
	s_mov_b32 m0, s41
	v_lshl_add_u64 v[6:7], s[44:45], 0, v[4:5]
	s_add_i32 s41, s1, 0x14000
	s_mov_b32 s42, m0
	s_mov_b32 m0, s41
	s_nop 0
	global_load_lds_dwordx4 v[6:7], off
	s_mov_b32 m0, s42
	v_lshl_add_u64 v[6:7], s[46:47], 0, v[4:5]
	s_add_i32 s42, s1, 0x1c000
	s_mov_b32 s43, m0
	s_mov_b32 m0, s42
	s_nop 0
	global_load_lds_dwordx4 v[6:7], off
	s_mov_b32 m0, s43
	v_lshl_add_u64 v[6:7], s[44:45], 0, v[146:147]
	s_add_i32 s43, s1, 0x16000
	s_mov_b32 s44, m0
	s_mov_b32 m0, s43
	s_nop 0
	global_load_lds_dwordx4 v[6:7], off
	s_mov_b32 m0, s44
	v_lshl_add_u64 v[6:7], s[46:47], 0, v[146:147]
	s_add_i32 s44, s1, 0x1e000
	s_mov_b32 s45, m0
	s_mov_b32 m0, s44
	s_nop 0
	global_load_lds_dwordx4 v[6:7], off
	s_mov_b32 m0, s45
	v_and_b32_e32 v182, 0xffffc000, v9
	v_or_b32_e32 v183, 0x800, v182
	v_or_b32_e32 v189, 0x1000, v182
	v_or_b32_e32 v199, 0x1800, v182
	v_or_b32_e32 v200, 0x2000, v182
	v_or_b32_e32 v201, 0x2800, v182
	v_or_b32_e32 v203, 0x3000, v182
	v_or_b32_e32 v206, 0x3800, v182
	s_movk_i32 s45, 0x6000
	v_and_or_b32 v7, v8, s45, v12
	ds_read_b128 v[8:11], v7 offset:32768
	v_or_b32_e32 v6, v12, v182
	ds_read_b128 v[12:15], v7 offset:34816
	ds_read_b128 v[16:19], v7 offset:36864
	ds_read_b128 v[24:27], v7 offset:38912
	ds_read_b128 v[20:23], v6
	ds_read_b128 v[28:31], v6 offset:2048
	ds_read_b128 v[32:35], v6 offset:4096
	ds_read_b128 v[36:39], v6 offset:6144
	s_waitcnt lgkmcnt(3)
	v_mfma_f32_16x16x32_bf16 v[40:43], v[8:11], v[20:23], 0
	v_mfma_f32_16x16x32_bf16 v[44:47], v[12:15], v[20:23], 0
	v_mfma_f32_16x16x32_bf16 v[48:51], v[16:19], v[20:23], 0
	v_mfma_f32_16x16x32_bf16 v[20:23], v[24:27], v[20:23], 0
	ds_read_b128 v[52:55], v6 offset:8192
	s_waitcnt lgkmcnt(3)
	v_mfma_f32_16x16x32_bf16 v[56:59], v[8:11], v[28:31], 0
	v_mfma_f32_16x16x32_bf16 v[60:63], v[12:15], v[28:31], 0
	v_mfma_f32_16x16x32_bf16 v[64:67], v[16:19], v[28:31], 0
	v_mfma_f32_16x16x32_bf16 v[28:31], v[24:27], v[28:31], 0
	ds_read_b128 v[68:71], v6 offset:10240
	s_waitcnt lgkmcnt(3)
	v_mfma_f32_16x16x32_bf16 v[72:75], v[8:11], v[32:35], 0
	v_mfma_f32_16x16x32_bf16 v[76:79], v[12:15], v[32:35], 0
	v_mfma_f32_16x16x32_bf16 v[80:83], v[16:19], v[32:35], 0
	v_mfma_f32_16x16x32_bf16 v[32:35], v[24:27], v[32:35], 0
	ds_read_b128 v[84:87], v6 offset:12288
	s_waitcnt lgkmcnt(3)
	v_mfma_f32_16x16x32_bf16 v[88:91], v[8:11], v[36:39], 0
	v_mfma_f32_16x16x32_bf16 v[92:95], v[12:15], v[36:39], 0
	v_mfma_f32_16x16x32_bf16 v[96:99], v[16:19], v[36:39], 0
	v_mfma_f32_16x16x32_bf16 v[36:39], v[24:27], v[36:39], 0
	ds_read_b128 v[100:103], v6 offset:14336
	s_waitcnt lgkmcnt(3)
	v_mfma_f32_16x16x32_bf16 v[104:107], v[8:11], v[52:55], 0
	v_mfma_f32_16x16x32_bf16 v[108:111], v[12:15], v[52:55], 0
	v_mfma_f32_16x16x32_bf16 v[112:115], v[16:19], v[52:55], 0
	v_mfma_f32_16x16x32_bf16 v[52:55], v[24:27], v[52:55], 0
	s_waitcnt lgkmcnt(2)
	v_mfma_f32_16x16x32_bf16 v[116:119], v[8:11], v[68:71], 0
	v_mfma_f32_16x16x32_bf16 v[120:123], v[12:15], v[68:71], 0
	v_mfma_f32_16x16x32_bf16 v[124:127], v[16:19], v[68:71], 0
	v_mfma_f32_16x16x32_bf16 v[68:71], v[24:27], v[68:71], 0
	s_waitcnt lgkmcnt(1)
	v_mfma_f32_16x16x32_bf16 v[128:131], v[8:11], v[84:87], 0
	v_mfma_f32_16x16x32_bf16 v[132:135], v[12:15], v[84:87], 0
	v_mfma_f32_16x16x32_bf16 v[136:139], v[16:19], v[84:87], 0
	v_mfma_f32_16x16x32_bf16 v[84:87], v[24:27], v[84:87], 0
	s_waitcnt lgkmcnt(0)
	v_mfma_f32_16x16x32_bf16 v[8:11], v[8:11], v[100:103], 0
	v_mfma_f32_16x16x32_bf16 v[12:15], v[12:15], v[100:103], 0
	v_mfma_f32_16x16x32_bf16 v[16:19], v[16:19], v[100:103], 0
	v_mfma_f32_16x16x32_bf16 v[24:27], v[24:27], v[100:103], 0
	ds_read_b128 v[100:103], v7 offset:33792
	ds_read_b128 v[140:143], v7 offset:35840
	ds_read_b128 v[150:153], v7 offset:37888
	ds_read_b128 v[158:161], v7 offset:39936
	ds_read_b128 v[154:157], v6 offset:1024
	ds_read_b128 v[162:165], v6 offset:3072
	ds_read_b128 v[166:169], v6 offset:5120
	ds_read_b128 v[170:173], v6 offset:7168
	s_waitcnt lgkmcnt(3)
	v_mfma_f32_16x16x32_bf16 v[40:43], v[100:103], v[154:157], v[40:43]
	v_mfma_f32_16x16x32_bf16 v[44:47], v[140:143], v[154:157], v[44:47]
	v_mfma_f32_16x16x32_bf16 v[48:51], v[150:153], v[154:157], v[48:51]
	v_mfma_f32_16x16x32_bf16 v[20:23], v[158:161], v[154:157], v[20:23]
	ds_read_b128 v[154:157], v6 offset:9216
	s_waitcnt lgkmcnt(3)
	v_mfma_f32_16x16x32_bf16 v[56:59], v[100:103], v[162:165], v[56:59]
	v_mfma_f32_16x16x32_bf16 v[60:63], v[140:143], v[162:165], v[60:63]
	v_mfma_f32_16x16x32_bf16 v[64:67], v[150:153], v[162:165], v[64:67]
	v_mfma_f32_16x16x32_bf16 v[28:31], v[158:161], v[162:165], v[28:31]
	ds_read_b128 v[162:165], v6 offset:11264
	s_waitcnt lgkmcnt(3)
	v_mfma_f32_16x16x32_bf16 v[72:75], v[100:103], v[166:169], v[72:75]
	v_mfma_f32_16x16x32_bf16 v[76:79], v[140:143], v[166:169], v[76:79]
	v_mfma_f32_16x16x32_bf16 v[80:83], v[150:153], v[166:169], v[80:83]
	v_mfma_f32_16x16x32_bf16 v[32:35], v[158:161], v[166:169], v[32:35]
	ds_read_b128 v[166:169], v6 offset:13312
	s_waitcnt lgkmcnt(3)
	v_mfma_f32_16x16x32_bf16 v[88:91], v[100:103], v[170:173], v[88:91]
	v_mfma_f32_16x16x32_bf16 v[92:95], v[140:143], v[170:173], v[92:95]
	v_mfma_f32_16x16x32_bf16 v[96:99], v[150:153], v[170:173], v[96:99]
	v_mfma_f32_16x16x32_bf16 v[36:39], v[158:161], v[170:173], v[36:39]
	ds_read_b128 v[170:173], v6 offset:15360
	s_waitcnt lgkmcnt(3)
	v_mfma_f32_16x16x32_bf16 v[104:107], v[100:103], v[154:157], v[104:107]
	v_mfma_f32_16x16x32_bf16 v[108:111], v[140:143], v[154:157], v[108:111]
	v_mfma_f32_16x16x32_bf16 v[112:115], v[150:153], v[154:157], v[112:115]
	v_mfma_f32_16x16x32_bf16 v[52:55], v[158:161], v[154:157], v[52:55]
	s_waitcnt lgkmcnt(2)
	v_mfma_f32_16x16x32_bf16 v[116:119], v[100:103], v[162:165], v[116:119]
	v_mfma_f32_16x16x32_bf16 v[120:123], v[140:143], v[162:165], v[120:123]
	v_mfma_f32_16x16x32_bf16 v[124:127], v[150:153], v[162:165], v[124:127]
	v_mfma_f32_16x16x32_bf16 v[68:71], v[158:161], v[162:165], v[68:71]
	s_waitcnt lgkmcnt(1)
	v_mfma_f32_16x16x32_bf16 v[128:131], v[100:103], v[166:169], v[128:131]
	v_mfma_f32_16x16x32_bf16 v[132:135], v[140:143], v[166:169], v[132:135]
	v_mfma_f32_16x16x32_bf16 v[136:139], v[150:153], v[166:169], v[136:139]
	v_mfma_f32_16x16x32_bf16 v[84:87], v[158:161], v[166:169], v[84:87]
	s_waitcnt lgkmcnt(0)
	v_mfma_f32_16x16x32_bf16 v[100:103], v[100:103], v[170:173], v[8:11]
	v_mfma_f32_16x16x32_bf16 v[150:153], v[150:153], v[170:173], v[16:19]
	v_mfma_f32_16x16x32_bf16 v[24:27], v[158:161], v[170:173], v[24:27]
	v_mfma_f32_16x16x32_bf16 v[140:143], v[140:143], v[170:173], v[12:15]
	s_add_u32 s46, s16, 0x100
	s_addc_u32 s47, s17, 0
	s_add_u32 s48, s18, 0x100
	s_waitcnt vmcnt(0)
	s_barrier
	s_addc_u32 s49, s19, 0
	v_lshl_add_u64 v[8:9], s[46:47], 0, v[0:1]
	s_mov_b32 s45, m0
	s_mov_b32 m0, s1
	s_nop 0
	global_load_lds_dwordx4 v[8:9], off
	s_mov_b32 m0, s45
	v_lshl_add_u64 v[8:9], s[48:49], 0, v[0:1]
	s_mov_b32 s45, m0
	s_mov_b32 m0, s30
	s_nop 0
	global_load_lds_dwordx4 v[8:9], off
	s_mov_b32 m0, s45
	v_lshl_add_u64 v[8:9], s[46:47], 0, v[2:3]
	s_mov_b32 s45, m0
	s_mov_b32 m0, s31
	s_nop 0
	global_load_lds_dwordx4 v[8:9], off
	s_mov_b32 m0, s45
	v_lshl_add_u64 v[8:9], s[48:49], 0, v[2:3]
	s_mov_b32 s45, m0
	s_mov_b32 m0, s34
	s_nop 0
	global_load_lds_dwordx4 v[8:9], off
	s_mov_b32 m0, s45
	v_lshl_add_u64 v[8:9], s[46:47], 0, v[4:5]
	s_mov_b32 s45, m0
	s_mov_b32 m0, s35
	s_nop 0
	global_load_lds_dwordx4 v[8:9], off
	s_mov_b32 m0, s45
	v_lshl_add_u64 v[8:9], s[48:49], 0, v[4:5]
	s_mov_b32 s45, m0
	s_mov_b32 m0, s36
	s_nop 0
	global_load_lds_dwordx4 v[8:9], off
	s_mov_b32 m0, s45
	v_lshl_add_u64 v[8:9], s[46:47], 0, v[146:147]
	s_mov_b32 s45, m0
	s_mov_b32 m0, s37
	s_nop 0
	global_load_lds_dwordx4 v[8:9], off
	s_mov_b32 m0, s45
	v_lshl_add_u64 v[8:9], s[48:49], 0, v[146:147]
	s_mov_b32 s45, m0
	s_mov_b32 m0, s38
	s_nop 0
	global_load_lds_dwordx4 v[8:9], off
	s_mov_b32 m0, s45
	v_or_b32_e32 v8, 0x18000, v7
	v_or_b32_e32 v9, 0x18800, v7
	v_or_b32_e32 v11, 0x19000, v7
	v_or_b32_e32 v10, 0x19800, v7
	ds_read_b128 v[154:157], v8
	ds_read_b128 v[158:161], v9
	ds_read_b128 v[162:165], v11
	ds_read_b128 v[166:169], v10
	v_bitop3_b32 v207, v145, s33, v149 bitop3:0xde
	v_add_u32_e32 v12, v207, v182
	ds_read_b128 v[16:19], v12
	v_add_u32_e32 v13, v207, v183
	v_add_u32_e32 v14, v207, v189
	v_add_u32_e32 v15, v207, v199
	ds_read_b128 v[170:173], v13
	ds_read_b128 v[174:177], v14
	ds_read_b128 v[178:181], v15
	s_waitcnt lgkmcnt(3)
	v_mfma_f32_16x16x32_bf16 v[40:43], v[154:157], v[16:19], v[40:43]
	v_mfma_f32_16x16x32_bf16 v[44:47], v[158:161], v[16:19], v[44:47]
	v_mfma_f32_16x16x32_bf16 v[48:51], v[162:165], v[16:19], v[48:51]
	v_mfma_f32_16x16x32_bf16 v[214:217], v[166:169], v[16:19], v[20:23]
	v_add_u32_e32 v16, v207, v200
	v_add_u32_e32 v17, v207, v201
	v_add_u32_e32 v18, v207, v203
	v_add_u32_e32 v19, v207, v206
	ds_read_b128 v[20:23], v16
	s_waitcnt lgkmcnt(3)
	v_mfma_f32_16x16x32_bf16 v[56:59], v[154:157], v[170:173], v[56:59]
	v_mfma_f32_16x16x32_bf16 v[60:63], v[158:161], v[170:173], v[60:63]
	v_mfma_f32_16x16x32_bf16 v[64:67], v[162:165], v[170:173], v[64:67]
	v_mfma_f32_16x16x32_bf16 v[170:173], v[166:169], v[170:173], v[28:31]
	s_nop 2
	ds_read_b128 v[28:31], v17
	s_waitcnt lgkmcnt(3)
	v_mfma_f32_16x16x32_bf16 v[72:75], v[154:157], v[174:177], v[72:75]
	v_mfma_f32_16x16x32_bf16 v[76:79], v[158:161], v[174:177], v[76:79]
	v_mfma_f32_16x16x32_bf16 v[80:83], v[162:165], v[174:177], v[80:83]
	v_mfma_f32_16x16x32_bf16 v[32:35], v[166:169], v[174:177], v[32:35]
	ds_read_b128 v[174:177], v18
	s_waitcnt lgkmcnt(3)
	v_mfma_f32_16x16x32_bf16 v[88:91], v[154:157], v[178:181], v[88:91]
	v_mfma_f32_16x16x32_bf16 v[92:95], v[158:161], v[178:181], v[92:95]
	v_mfma_f32_16x16x32_bf16 v[96:99], v[162:165], v[178:181], v[96:99]
	v_mfma_f32_16x16x32_bf16 v[36:39], v[166:169], v[178:181], v[36:39]
	ds_read_b128 v[178:181], v19
	s_waitcnt lgkmcnt(3)
	v_mfma_f32_16x16x32_bf16 v[104:107], v[154:157], v[20:23], v[104:107]
	v_mfma_f32_16x16x32_bf16 v[108:111], v[158:161], v[20:23], v[108:111]
	v_mfma_f32_16x16x32_bf16 v[112:115], v[162:165], v[20:23], v[112:115]
	v_mfma_f32_16x16x32_bf16 v[52:55], v[166:169], v[20:23], v[52:55]
	s_waitcnt lgkmcnt(2)
	v_mfma_f32_16x16x32_bf16 v[116:119], v[154:157], v[28:31], v[116:119]
	v_mfma_f32_16x16x32_bf16 v[120:123], v[158:161], v[28:31], v[120:123]
	v_mfma_f32_16x16x32_bf16 v[124:127], v[162:165], v[28:31], v[124:127]
	v_mfma_f32_16x16x32_bf16 v[68:71], v[166:169], v[28:31], v[68:71]
	s_waitcnt lgkmcnt(1)
	v_mfma_f32_16x16x32_bf16 v[128:131], v[154:157], v[174:177], v[128:131]
	v_mfma_f32_16x16x32_bf16 v[132:135], v[158:161], v[174:177], v[132:135]
	v_mfma_f32_16x16x32_bf16 v[84:87], v[166:169], v[174:177], v[84:87]
	s_waitcnt lgkmcnt(0)
	v_mfma_f32_16x16x32_bf16 v[100:103], v[154:157], v[178:181], v[100:103]
	v_mfma_f32_16x16x32_bf16 v[150:153], v[162:165], v[178:181], v[150:153]
	v_mfma_f32_16x16x32_bf16 v[154:157], v[166:169], v[178:181], v[24:27]
	v_mfma_f32_16x16x32_bf16 v[136:139], v[162:165], v[174:177], v[136:139]
	v_mfma_f32_16x16x32_bf16 v[140:143], v[158:161], v[178:181], v[140:143]
	v_or_b32_e32 v20, 0x18400, v7
	v_or_b32_e32 v21, 0x18c00, v7
	v_or_b32_e32 v23, 0x19400, v7
	v_or_b32_e32 v22, 0x19c00, v7
	ds_read_b128 v[158:161], v20
	ds_read_b128 v[162:165], v21
	ds_read_b128 v[166:169], v23
	ds_read_b128 v[174:177], v22
	s_mov_b32 s45, 0x10400
	v_bitop3_b32 v145, v145, s45, v149 bitop3:0xde
	v_add_u32_e32 v24, v145, v182
	ds_read_b128 v[28:31], v24
	v_add_u32_e32 v25, v145, v183
	v_add_u32_e32 v26, v145, v189
	v_add_u32_e32 v27, v145, v199
	ds_read_b128 v[178:181], v25
	ds_read_b128 v[218:221], v26
	ds_read_b128 v[222:225], v27
	s_waitcnt lgkmcnt(3)
	v_mfma_f32_16x16x32_bf16 v[40:43], v[158:161], v[28:31], v[40:43]
	v_mfma_f32_16x16x32_bf16 v[44:47], v[162:165], v[28:31], v[44:47]
	v_mfma_f32_16x16x32_bf16 v[48:51], v[166:169], v[28:31], v[48:51]
	v_mfma_f32_16x16x32_bf16 v[214:217], v[174:177], v[28:31], v[214:217]
	v_add_u32_e32 v28, v145, v200
	v_add_u32_e32 v29, v145, v201
	v_add_u32_e32 v30, v145, v203
	v_add_u32_e32 v31, v145, v206
	ds_read_b128 v[226:229], v28
	s_waitcnt lgkmcnt(3)
	v_mfma_f32_16x16x32_bf16 v[56:59], v[158:161], v[178:181], v[56:59]
	v_mfma_f32_16x16x32_bf16 v[60:63], v[162:165], v[178:181], v[60:63]
	v_mfma_f32_16x16x32_bf16 v[64:67], v[166:169], v[178:181], v[64:67]
	v_mfma_f32_16x16x32_bf16 v[170:173], v[174:177], v[178:181], v[170:173]
	ds_read_b128 v[178:181], v29
	s_waitcnt lgkmcnt(3)
	v_mfma_f32_16x16x32_bf16 v[72:75], v[158:161], v[218:221], v[72:75]
	v_mfma_f32_16x16x32_bf16 v[76:79], v[162:165], v[218:221], v[76:79]
	v_mfma_f32_16x16x32_bf16 v[80:83], v[166:169], v[218:221], v[80:83]
	v_mfma_f32_16x16x32_bf16 v[32:35], v[174:177], v[218:221], v[32:35]
	ds_read_b128 v[218:221], v30
	s_waitcnt lgkmcnt(3)
	v_mfma_f32_16x16x32_bf16 v[88:91], v[158:161], v[222:225], v[88:91]
	v_mfma_f32_16x16x32_bf16 v[92:95], v[162:165], v[222:225], v[92:95]
	v_mfma_f32_16x16x32_bf16 v[96:99], v[166:169], v[222:225], v[96:99]
	v_mfma_f32_16x16x32_bf16 v[36:39], v[174:177], v[222:225], v[36:39]
	ds_read_b128 v[222:225], v31
	s_waitcnt lgkmcnt(3)
	v_mfma_f32_16x16x32_bf16 v[104:107], v[158:161], v[226:229], v[104:107]
	v_mfma_f32_16x16x32_bf16 v[108:111], v[162:165], v[226:229], v[108:111]
	v_mfma_f32_16x16x32_bf16 v[112:115], v[166:169], v[226:229], v[112:115]
	v_mfma_f32_16x16x32_bf16 v[52:55], v[174:177], v[226:229], v[52:55]
	s_waitcnt lgkmcnt(2)
	v_mfma_f32_16x16x32_bf16 v[116:119], v[158:161], v[178:181], v[116:119]
	v_mfma_f32_16x16x32_bf16 v[120:123], v[162:165], v[178:181], v[120:123]
	v_mfma_f32_16x16x32_bf16 v[124:127], v[166:169], v[178:181], v[124:127]
	v_mfma_f32_16x16x32_bf16 v[68:71], v[174:177], v[178:181], v[68:71]
	s_waitcnt lgkmcnt(1)
	v_mfma_f32_16x16x32_bf16 v[132:135], v[162:165], v[218:221], v[132:135]
	v_mfma_f32_16x16x32_bf16 v[84:87], v[174:177], v[218:221], v[84:87]
	s_waitcnt lgkmcnt(0)
	v_mfma_f32_16x16x32_bf16 v[100:103], v[158:161], v[222:225], v[100:103]
	v_mfma_f32_16x16x32_bf16 v[150:153], v[166:169], v[222:225], v[150:153]
	v_mfma_f32_16x16x32_bf16 v[154:157], v[174:177], v[222:225], v[154:157]
	v_mfma_f32_16x16x32_bf16 v[128:131], v[158:161], v[218:221], v[128:131]
	v_mfma_f32_16x16x32_bf16 v[136:139], v[166:169], v[218:221], v[136:139]
	v_mfma_f32_16x16x32_bf16 v[140:143], v[162:165], v[222:225], v[140:143]
	s_add_u32 s46, s16, 0x180
	s_addc_u32 s47, s17, 0
	s_add_u32 s48, s18, 0x180
	s_waitcnt vmcnt(0)
	s_barrier
	s_addc_u32 s49, s19, 0
	v_lshl_add_u64 v[158:159], s[46:47], 0, v[0:1]
	s_mov_b32 s45, m0
	s_mov_b32 m0, s25
	s_nop 0
	global_load_lds_dwordx4 v[158:159], off
	s_mov_b32 m0, s45
	v_lshl_add_u64 v[158:159], s[48:49], 0, v[0:1]
	s_mov_b32 s45, m0
	s_mov_b32 m0, s24
	s_nop 0
	global_load_lds_dwordx4 v[158:159], off
	s_mov_b32 m0, s45
	v_lshl_add_u64 v[158:159], s[46:47], 0, v[2:3]
	s_mov_b32 s45, m0
	s_mov_b32 m0, s39
	s_nop 0
	global_load_lds_dwordx4 v[158:159], off
	s_mov_b32 m0, s45
	v_lshl_add_u64 v[158:159], s[48:49], 0, v[2:3]
	s_mov_b32 s45, m0
	s_mov_b32 m0, s40
	s_nop 0
	global_load_lds_dwordx4 v[158:159], off
	s_mov_b32 m0, s45
	v_lshl_add_u64 v[158:159], s[46:47], 0, v[4:5]
	s_mov_b32 s45, m0
	s_mov_b32 m0, s41
	s_nop 0
	global_load_lds_dwordx4 v[158:159], off
	s_mov_b32 m0, s45
	v_lshl_add_u64 v[158:159], s[48:49], 0, v[4:5]
	s_mov_b32 s45, m0
	s_mov_b32 m0, s42
	s_nop 0
	global_load_lds_dwordx4 v[158:159], off
	s_mov_b32 m0, s45
	v_lshl_add_u64 v[158:159], s[46:47], 0, v[146:147]
	s_mov_b32 s45, m0
	s_mov_b32 m0, s43
	s_nop 0
	global_load_lds_dwordx4 v[158:159], off
	s_mov_b32 m0, s45
	v_lshl_add_u64 v[158:159], s[48:49], 0, v[146:147]
	s_mov_b32 s45, m0
	s_mov_b32 m0, s44
	s_nop 0
	global_load_lds_dwordx4 v[158:159], off
	s_mov_b32 m0, s45
	ds_read_b128 v[158:161], v7 offset:32768
	ds_read_b128 v[162:165], v7 offset:34816
	ds_read_b128 v[166:169], v7 offset:36864
	ds_read_b128 v[178:181], v7 offset:38912
	ds_read_b128 v[174:177], v6
	ds_read_b128 v[218:221], v6 offset:2048
	ds_read_b128 v[222:225], v6 offset:4096
	ds_read_b128 v[226:229], v6 offset:6144
	s_waitcnt lgkmcnt(3)
	v_mfma_f32_16x16x32_bf16 v[40:43], v[158:161], v[174:177], v[40:43]
	v_mfma_f32_16x16x32_bf16 v[44:47], v[162:165], v[174:177], v[44:47]
	v_mfma_f32_16x16x32_bf16 v[48:51], v[166:169], v[174:177], v[48:51]
	v_mfma_f32_16x16x32_bf16 v[174:177], v[178:181], v[174:177], v[214:217]
	s_nop 2
	ds_read_b128 v[214:217], v6 offset:8192
	s_waitcnt lgkmcnt(3)
	v_mfma_f32_16x16x32_bf16 v[56:59], v[158:161], v[218:221], v[56:59]
	v_mfma_f32_16x16x32_bf16 v[60:63], v[162:165], v[218:221], v[60:63]
	v_mfma_f32_16x16x32_bf16 v[64:67], v[166:169], v[218:221], v[64:67]
	v_mfma_f32_16x16x32_bf16 v[170:173], v[178:181], v[218:221], v[170:173]
	ds_read_b128 v[218:221], v6 offset:10240
	s_waitcnt lgkmcnt(3)
	v_mfma_f32_16x16x32_bf16 v[72:75], v[158:161], v[222:225], v[72:75]
	v_mfma_f32_16x16x32_bf16 v[76:79], v[162:165], v[222:225], v[76:79]
	v_mfma_f32_16x16x32_bf16 v[80:83], v[166:169], v[222:225], v[80:83]
	v_mfma_f32_16x16x32_bf16 v[32:35], v[178:181], v[222:225], v[32:35]
	ds_read_b128 v[222:225], v6 offset:12288
	s_waitcnt lgkmcnt(3)
	v_mfma_f32_16x16x32_bf16 v[88:91], v[158:161], v[226:229], v[88:91]
	v_mfma_f32_16x16x32_bf16 v[92:95], v[162:165], v[226:229], v[92:95]
	v_mfma_f32_16x16x32_bf16 v[96:99], v[166:169], v[226:229], v[96:99]
	v_mfma_f32_16x16x32_bf16 v[36:39], v[178:181], v[226:229], v[36:39]
	ds_read_b128 v[226:229], v6 offset:14336
	s_waitcnt lgkmcnt(3)
	v_mfma_f32_16x16x32_bf16 v[104:107], v[158:161], v[214:217], v[104:107]
	v_mfma_f32_16x16x32_bf16 v[108:111], v[162:165], v[214:217], v[108:111]
	v_mfma_f32_16x16x32_bf16 v[112:115], v[166:169], v[214:217], v[112:115]
	v_mfma_f32_16x16x32_bf16 v[52:55], v[178:181], v[214:217], v[52:55]
	s_waitcnt lgkmcnt(2)
	v_mfma_f32_16x16x32_bf16 v[116:119], v[158:161], v[218:221], v[116:119]
	v_mfma_f32_16x16x32_bf16 v[120:123], v[162:165], v[218:221], v[120:123]
	v_mfma_f32_16x16x32_bf16 v[124:127], v[166:169], v[218:221], v[124:127]
	v_mfma_f32_16x16x32_bf16 v[68:71], v[178:181], v[218:221], v[68:71]
	s_waitcnt lgkmcnt(1)
	v_mfma_f32_16x16x32_bf16 v[132:135], v[162:165], v[222:225], v[132:135]
	v_mfma_f32_16x16x32_bf16 v[84:87], v[178:181], v[222:225], v[84:87]
	s_waitcnt lgkmcnt(0)
	v_mfma_f32_16x16x32_bf16 v[100:103], v[158:161], v[226:229], v[100:103]
	v_mfma_f32_16x16x32_bf16 v[150:153], v[166:169], v[226:229], v[150:153]
	v_mfma_f32_16x16x32_bf16 v[154:157], v[178:181], v[226:229], v[154:157]
	v_mfma_f32_16x16x32_bf16 v[128:131], v[158:161], v[222:225], v[128:131]
	v_mfma_f32_16x16x32_bf16 v[136:139], v[166:169], v[222:225], v[136:139]
	v_mfma_f32_16x16x32_bf16 v[140:143], v[162:165], v[226:229], v[140:143]
	ds_read_b128 v[158:161], v7 offset:33792
	ds_read_b128 v[162:165], v7 offset:35840
	ds_read_b128 v[166:169], v7 offset:37888
	ds_read_b128 v[214:217], v7 offset:39936
	ds_read_b128 v[178:181], v6 offset:1024
	ds_read_b128 v[218:221], v6 offset:3072
	ds_read_b128 v[222:225], v6 offset:5120
	ds_read_b128 v[226:229], v6 offset:7168
	s_waitcnt lgkmcnt(3)
	v_mfma_f32_16x16x32_bf16 v[40:43], v[158:161], v[178:181], v[40:43]
	v_mfma_f32_16x16x32_bf16 v[44:47], v[162:165], v[178:181], v[44:47]
	v_mfma_f32_16x16x32_bf16 v[48:51], v[166:169], v[178:181], v[48:51]
	v_mfma_f32_16x16x32_bf16 v[174:177], v[214:217], v[178:181], v[174:177]
	ds_read_b128 v[178:181], v6 offset:9216
	s_waitcnt lgkmcnt(3)
	v_mfma_f32_16x16x32_bf16 v[56:59], v[158:161], v[218:221], v[56:59]
	v_mfma_f32_16x16x32_bf16 v[60:63], v[162:165], v[218:221], v[60:63]
	v_mfma_f32_16x16x32_bf16 v[64:67], v[166:169], v[218:221], v[64:67]
	v_mfma_f32_16x16x32_bf16 v[170:173], v[214:217], v[218:221], v[170:173]
	ds_read_b128 v[218:221], v6 offset:11264
	s_waitcnt lgkmcnt(3)
	v_mfma_f32_16x16x32_bf16 v[72:75], v[158:161], v[222:225], v[72:75]
	v_mfma_f32_16x16x32_bf16 v[76:79], v[162:165], v[222:225], v[76:79]
	v_mfma_f32_16x16x32_bf16 v[80:83], v[166:169], v[222:225], v[80:83]
	v_mfma_f32_16x16x32_bf16 v[32:35], v[214:217], v[222:225], v[32:35]
	ds_read_b128 v[222:225], v6 offset:13312
	s_waitcnt lgkmcnt(3)
	v_mfma_f32_16x16x32_bf16 v[88:91], v[158:161], v[226:229], v[88:91]
	v_mfma_f32_16x16x32_bf16 v[92:95], v[162:165], v[226:229], v[92:95]
	v_mfma_f32_16x16x32_bf16 v[96:99], v[166:169], v[226:229], v[96:99]
	v_mfma_f32_16x16x32_bf16 v[36:39], v[214:217], v[226:229], v[36:39]
	ds_read_b128 v[226:229], v6 offset:15360
	s_waitcnt lgkmcnt(3)
	v_mfma_f32_16x16x32_bf16 v[104:107], v[158:161], v[178:181], v[104:107]
	v_mfma_f32_16x16x32_bf16 v[108:111], v[162:165], v[178:181], v[108:111]
	v_mfma_f32_16x16x32_bf16 v[112:115], v[166:169], v[178:181], v[112:115]
	v_mfma_f32_16x16x32_bf16 v[52:55], v[214:217], v[178:181], v[52:55]
	s_waitcnt lgkmcnt(2)
	v_mfma_f32_16x16x32_bf16 v[116:119], v[158:161], v[218:221], v[116:119]
	v_mfma_f32_16x16x32_bf16 v[120:123], v[162:165], v[218:221], v[120:123]
	v_mfma_f32_16x16x32_bf16 v[124:127], v[166:169], v[218:221], v[124:127]
	v_mfma_f32_16x16x32_bf16 v[68:71], v[214:217], v[218:221], v[68:71]
	s_waitcnt lgkmcnt(1)
	v_mfma_f32_16x16x32_bf16 v[132:135], v[162:165], v[222:225], v[132:135]
	v_mfma_f32_16x16x32_bf16 v[84:87], v[214:217], v[222:225], v[84:87]
	s_waitcnt lgkmcnt(0)
	v_mfma_f32_16x16x32_bf16 v[100:103], v[158:161], v[226:229], v[100:103]
	v_mfma_f32_16x16x32_bf16 v[150:153], v[166:169], v[226:229], v[150:153]
	v_mfma_f32_16x16x32_bf16 v[154:157], v[214:217], v[226:229], v[154:157]
	v_mfma_f32_16x16x32_bf16 v[128:131], v[158:161], v[222:225], v[128:131]
	v_mfma_f32_16x16x32_bf16 v[136:139], v[166:169], v[222:225], v[136:139]
	v_mfma_f32_16x16x32_bf16 v[140:143], v[162:165], v[226:229], v[140:143]
	s_add_u32 s46, s16, 0x200
	s_addc_u32 s47, s17, 0
	s_add_u32 s48, s18, 0x200
	s_waitcnt vmcnt(0)
	s_barrier
	s_addc_u32 s49, s19, 0
	ds_read_b128 v[158:161], v8
	ds_read_b128 v[162:165], v12
	ds_read_b128 v[166:169], v9
	ds_read_b128 v[178:181], v13
	ds_read_b128 v[214:217], v11
	ds_read_b128 v[218:221], v10
	ds_read_b128 v[222:225], v14
	ds_read_b128 v[226:229], v15
	s_waitcnt lgkmcnt(6)
	v_mfma_f32_16x16x32_bf16 v[40:43], v[158:161], v[162:165], v[40:43]
	s_waitcnt lgkmcnt(5)
	v_mfma_f32_16x16x32_bf16 v[44:47], v[166:169], v[162:165], v[44:47]
	s_waitcnt lgkmcnt(4)
	v_mfma_f32_16x16x32_bf16 v[56:59], v[158:161], v[178:181], v[56:59]
	s_mov_b32 m0, s1
	v_mfma_f32_16x16x32_bf16 v[60:63], v[166:169], v[178:181], v[60:63]
	global_load_lds_dwordx4 v0, s[46:47]
	s_waitcnt lgkmcnt(3)
	v_mfma_f32_16x16x32_bf16 v[48:51], v[214:217], v[162:165], v[48:51]
	v_mfma_f32_16x16x32_bf16 v[64:67], v[214:217], v[178:181], v[64:67]
	s_waitcnt lgkmcnt(2)
	v_mfma_f32_16x16x32_bf16 v[174:177], v[218:221], v[162:165], v[174:177]
	ds_read_b128 v[162:165], v16
	v_mfma_f32_16x16x32_bf16 v[170:173], v[218:221], v[178:181], v[170:173]
	ds_read_b128 v[178:181], v17
	s_waitcnt lgkmcnt(3)
	s_mov_b32 m0, s30
	v_mfma_f32_16x16x32_bf16 v[72:75], v[158:161], v[222:225], v[72:75]
	global_load_lds_dwordx4 v0, s[48:49]
	v_mfma_f32_16x16x32_bf16 v[76:79], v[166:169], v[222:225], v[76:79]
	v_mfma_f32_16x16x32_bf16 v[80:83], v[214:217], v[222:225], v[80:83]
	v_mfma_f32_16x16x32_bf16 v[32:35], v[218:221], v[222:225], v[32:35]
	ds_read_b128 v[222:225], v18
	s_waitcnt lgkmcnt(3)
	v_mfma_f32_16x16x32_bf16 v[88:91], v[158:161], v[226:229], v[88:91]
	s_mov_b32 m0, s31
	v_mfma_f32_16x16x32_bf16 v[92:95], v[166:169], v[226:229], v[92:95]
	global_load_lds_dwordx4 v2, s[46:47]
	v_mfma_f32_16x16x32_bf16 v[96:99], v[214:217], v[226:229], v[96:99]
	v_mfma_f32_16x16x32_bf16 v[36:39], v[218:221], v[226:229], v[36:39]
	ds_read_b128 v[226:229], v19
	s_waitcnt lgkmcnt(3)
	v_mfma_f32_16x16x32_bf16 v[104:107], v[158:161], v[162:165], v[104:107]
	s_waitcnt lgkmcnt(2)
	v_mfma_f32_16x16x32_bf16 v[116:119], v[158:161], v[178:181], v[116:119]
	s_waitcnt lgkmcnt(1)
	s_mov_b32 m0, s34
	v_mfma_f32_16x16x32_bf16 v[128:131], v[158:161], v[222:225], v[128:131]
	global_load_lds_dwordx4 v2, s[48:49]
	s_waitcnt lgkmcnt(0)
	v_mfma_f32_16x16x32_bf16 v[100:103], v[158:161], v[226:229], v[100:103]
	ds_read_b128 v[158:161], v20
	v_mfma_f32_16x16x32_bf16 v[108:111], v[166:169], v[162:165], v[108:111]
	v_mfma_f32_16x16x32_bf16 v[120:123], v[166:169], v[178:181], v[120:123]
	v_mfma_f32_16x16x32_bf16 v[132:135], v[166:169], v[222:225], v[132:135]
	s_mov_b32 m0, s35
	v_mfma_f32_16x16x32_bf16 v[140:143], v[166:169], v[226:229], v[140:143]
	global_load_lds_dwordx4 v4, s[46:47]
	ds_read_b128 v[166:169], v24
	v_mfma_f32_16x16x32_bf16 v[112:115], v[214:217], v[162:165], v[112:115]
	v_mfma_f32_16x16x32_bf16 v[52:55], v[218:221], v[162:165], v[52:55]
	ds_read_b128 v[162:165], v21
	v_mfma_f32_16x16x32_bf16 v[124:127], v[214:217], v[178:181], v[124:127]
	v_mfma_f32_16x16x32_bf16 v[68:71], v[218:221], v[178:181], v[68:71]
	ds_read_b128 v[178:181], v25
	s_mov_b32 m0, s36
	v_mfma_f32_16x16x32_bf16 v[136:139], v[214:217], v[222:225], v[136:139]
	global_load_lds_dwordx4 v4, s[48:49]
	v_mfma_f32_16x16x32_bf16 v[84:87], v[218:221], v[222:225], v[84:87]
	ds_read_b128 v[222:225], v26
	v_mfma_f32_16x16x32_bf16 v[150:153], v[214:217], v[226:229], v[150:153]
	ds_read_b128 v[214:217], v23
	v_mfma_f32_16x16x32_bf16 v[154:157], v[218:221], v[226:229], v[154:157]
	ds_read_b128 v[218:221], v22
	ds_read_b128 v[226:229], v27
	s_waitcnt lgkmcnt(6)
	v_mfma_f32_16x16x32_bf16 v[40:43], v[158:161], v[166:169], v[40:43]
	s_waitcnt lgkmcnt(5)
	s_mov_b32 m0, s37
	v_mfma_f32_16x16x32_bf16 v[44:47], v[162:165], v[166:169], v[44:47]
	global_load_lds_dwordx4 v146, s[46:47]
	s_waitcnt lgkmcnt(4)
	v_mfma_f32_16x16x32_bf16 v[56:59], v[158:161], v[178:181], v[56:59]
	v_mfma_f32_16x16x32_bf16 v[60:63], v[162:165], v[178:181], v[60:63]
	s_waitcnt lgkmcnt(3)
	v_mfma_f32_16x16x32_bf16 v[72:75], v[158:161], v[222:225], v[72:75]
	v_mfma_f32_16x16x32_bf16 v[76:79], v[162:165], v[222:225], v[76:79]
	s_waitcnt lgkmcnt(2)
	s_mov_b32 m0, s38
	v_mfma_f32_16x16x32_bf16 v[48:51], v[214:217], v[166:169], v[48:51]
	global_load_lds_dwordx4 v146, s[48:49]
	s_waitcnt lgkmcnt(1)
	v_mfma_f32_16x16x32_bf16 v[174:177], v[218:221], v[166:169], v[174:177]
	ds_read_b128 v[166:169], v28
	v_mfma_f32_16x16x32_bf16 v[64:67], v[214:217], v[178:181], v[64:67]
	v_mfma_f32_16x16x32_bf16 v[170:173], v[218:221], v[178:181], v[170:173]
	ds_read_b128 v[178:181], v29
	v_mfma_f32_16x16x32_bf16 v[80:83], v[214:217], v[222:225], v[80:83]
	v_mfma_f32_16x16x32_bf16 v[32:35], v[218:221], v[222:225], v[32:35]
	ds_read_b128 v[222:225], v30
	s_waitcnt lgkmcnt(3)
	v_mfma_f32_16x16x32_bf16 v[88:91], v[158:161], v[226:229], v[88:91]
	v_mfma_f32_16x16x32_bf16 v[92:95], v[162:165], v[226:229], v[92:95]
	v_mfma_f32_16x16x32_bf16 v[96:99], v[214:217], v[226:229], v[96:99]
	v_mfma_f32_16x16x32_bf16 v[36:39], v[218:221], v[226:229], v[36:39]
	ds_read_b128 v[226:229], v31
	s_waitcnt lgkmcnt(3)
	v_mfma_f32_16x16x32_bf16 v[104:107], v[158:161], v[166:169], v[104:107]
	v_mfma_f32_16x16x32_bf16 v[108:111], v[162:165], v[166:169], v[108:111]
	v_mfma_f32_16x16x32_bf16 v[112:115], v[214:217], v[166:169], v[112:115]
	v_mfma_f32_16x16x32_bf16 v[52:55], v[218:221], v[166:169], v[52:55]
	s_waitcnt lgkmcnt(2)
	v_mfma_f32_16x16x32_bf16 v[116:119], v[158:161], v[178:181], v[116:119]
	v_mfma_f32_16x16x32_bf16 v[120:123], v[162:165], v[178:181], v[120:123]
	v_mfma_f32_16x16x32_bf16 v[124:127], v[214:217], v[178:181], v[124:127]
	v_mfma_f32_16x16x32_bf16 v[68:71], v[218:221], v[178:181], v[68:71]
	s_waitcnt lgkmcnt(1)
	v_mfma_f32_16x16x32_bf16 v[128:131], v[158:161], v[222:225], v[128:131]
	v_mfma_f32_16x16x32_bf16 v[132:135], v[162:165], v[222:225], v[132:135]
	v_mfma_f32_16x16x32_bf16 v[136:139], v[214:217], v[222:225], v[136:139]
	v_mfma_f32_16x16x32_bf16 v[84:87], v[218:221], v[222:225], v[84:87]
	s_waitcnt lgkmcnt(0)
	v_mfma_f32_16x16x32_bf16 v[100:103], v[158:161], v[226:229], v[100:103]
	v_mfma_f32_16x16x32_bf16 v[140:143], v[162:165], v[226:229], v[140:143]
	v_mfma_f32_16x16x32_bf16 v[150:153], v[214:217], v[226:229], v[150:153]
	v_mfma_f32_16x16x32_bf16 v[154:157], v[218:221], v[226:229], v[154:157]
	s_add_u32 s46, s16, 0x280
	s_addc_u32 s47, s17, 0
	s_add_u32 s48, s18, 0x280
	s_waitcnt vmcnt(0)
	s_barrier
	s_addc_u32 s49, s19, 0
	ds_read_b128 v[158:161], v7 offset:32768
	ds_read_b128 v[162:165], v6
	ds_read_b128 v[166:169], v7 offset:34816
	ds_read_b128 v[178:181], v6 offset:2048
	ds_read_b128 v[214:217], v7 offset:36864
	ds_read_b128 v[218:221], v7 offset:38912
	ds_read_b128 v[222:225], v6 offset:4096
	ds_read_b128 v[226:229], v6 offset:6144
	s_waitcnt lgkmcnt(6)
	v_mfma_f32_16x16x32_bf16 v[40:43], v[158:161], v[162:165], v[40:43]
	s_waitcnt lgkmcnt(5)
	v_mfma_f32_16x16x32_bf16 v[44:47], v[166:169], v[162:165], v[44:47]
	s_waitcnt lgkmcnt(4)
	v_mfma_f32_16x16x32_bf16 v[56:59], v[158:161], v[178:181], v[56:59]
	s_mov_b32 m0, s25
	v_mfma_f32_16x16x32_bf16 v[60:63], v[166:169], v[178:181], v[60:63]
	global_load_lds_dwordx4 v0, s[46:47]
	s_waitcnt lgkmcnt(3)
	v_mfma_f32_16x16x32_bf16 v[48:51], v[214:217], v[162:165], v[48:51]
	v_mfma_f32_16x16x32_bf16 v[64:67], v[214:217], v[178:181], v[64:67]
	s_waitcnt lgkmcnt(2)
	v_mfma_f32_16x16x32_bf16 v[174:177], v[218:221], v[162:165], v[174:177]
	ds_read_b128 v[162:165], v6 offset:8192
	v_mfma_f32_16x16x32_bf16 v[170:173], v[218:221], v[178:181], v[170:173]
	ds_read_b128 v[178:181], v6 offset:10240
	s_waitcnt lgkmcnt(3)
	s_mov_b32 m0, s24
	v_mfma_f32_16x16x32_bf16 v[72:75], v[158:161], v[222:225], v[72:75]
	global_load_lds_dwordx4 v0, s[48:49]
	v_mfma_f32_16x16x32_bf16 v[76:79], v[166:169], v[222:225], v[76:79]
	v_mfma_f32_16x16x32_bf16 v[80:83], v[214:217], v[222:225], v[80:83]
	v_mfma_f32_16x16x32_bf16 v[32:35], v[218:221], v[222:225], v[32:35]
	ds_read_b128 v[222:225], v6 offset:12288
	s_waitcnt lgkmcnt(3)
	v_mfma_f32_16x16x32_bf16 v[88:91], v[158:161], v[226:229], v[88:91]
	s_mov_b32 m0, s39
	v_mfma_f32_16x16x32_bf16 v[92:95], v[166:169], v[226:229], v[92:95]
	global_load_lds_dwordx4 v2, s[46:47]
	v_mfma_f32_16x16x32_bf16 v[96:99], v[214:217], v[226:229], v[96:99]
	v_mfma_f32_16x16x32_bf16 v[36:39], v[218:221], v[226:229], v[36:39]
	ds_read_b128 v[226:229], v6 offset:14336
	s_waitcnt lgkmcnt(3)
	v_mfma_f32_16x16x32_bf16 v[104:107], v[158:161], v[162:165], v[104:107]
	s_waitcnt lgkmcnt(2)
	v_mfma_f32_16x16x32_bf16 v[116:119], v[158:161], v[178:181], v[116:119]
	s_waitcnt lgkmcnt(1)
	s_mov_b32 m0, s40
	v_mfma_f32_16x16x32_bf16 v[128:131], v[158:161], v[222:225], v[128:131]
	global_load_lds_dwordx4 v2, s[48:49]
	s_waitcnt lgkmcnt(0)
	v_mfma_f32_16x16x32_bf16 v[100:103], v[158:161], v[226:229], v[100:103]
	ds_read_b128 v[158:161], v7 offset:33792
	v_mfma_f32_16x16x32_bf16 v[108:111], v[166:169], v[162:165], v[108:111]
	v_mfma_f32_16x16x32_bf16 v[120:123], v[166:169], v[178:181], v[120:123]
	v_mfma_f32_16x16x32_bf16 v[132:135], v[166:169], v[222:225], v[132:135]
	s_mov_b32 m0, s41
	v_mfma_f32_16x16x32_bf16 v[140:143], v[166:169], v[226:229], v[140:143]
	global_load_lds_dwordx4 v4, s[46:47]
	ds_read_b128 v[166:169], v6 offset:1024
	v_mfma_f32_16x16x32_bf16 v[112:115], v[214:217], v[162:165], v[112:115]
	v_mfma_f32_16x16x32_bf16 v[52:55], v[218:221], v[162:165], v[52:55]
	ds_read_b128 v[162:165], v7 offset:35840
	v_mfma_f32_16x16x32_bf16 v[124:127], v[214:217], v[178:181], v[124:127]
	v_mfma_f32_16x16x32_bf16 v[68:71], v[218:221], v[178:181], v[68:71]
	ds_read_b128 v[178:181], v6 offset:3072
	s_mov_b32 m0, s42
	v_mfma_f32_16x16x32_bf16 v[136:139], v[214:217], v[222:225], v[136:139]
	global_load_lds_dwordx4 v4, s[48:49]
	v_mfma_f32_16x16x32_bf16 v[84:87], v[218:221], v[222:225], v[84:87]
	ds_read_b128 v[222:225], v6 offset:5120
	v_mfma_f32_16x16x32_bf16 v[150:153], v[214:217], v[226:229], v[150:153]
	ds_read_b128 v[214:217], v7 offset:37888
	v_mfma_f32_16x16x32_bf16 v[154:157], v[218:221], v[226:229], v[154:157]
	ds_read_b128 v[218:221], v7 offset:39936
	ds_read_b128 v[226:229], v6 offset:7168
	s_waitcnt lgkmcnt(6)
	v_mfma_f32_16x16x32_bf16 v[40:43], v[158:161], v[166:169], v[40:43]
	s_waitcnt lgkmcnt(5)
	s_mov_b32 m0, s43
	v_mfma_f32_16x16x32_bf16 v[44:47], v[162:165], v[166:169], v[44:47]
	global_load_lds_dwordx4 v146, s[46:47]
	s_waitcnt lgkmcnt(4)
	v_mfma_f32_16x16x32_bf16 v[56:59], v[158:161], v[178:181], v[56:59]
	v_mfma_f32_16x16x32_bf16 v[60:63], v[162:165], v[178:181], v[60:63]
	s_waitcnt lgkmcnt(3)
	v_mfma_f32_16x16x32_bf16 v[72:75], v[158:161], v[222:225], v[72:75]
	v_mfma_f32_16x16x32_bf16 v[76:79], v[162:165], v[222:225], v[76:79]
	s_waitcnt lgkmcnt(2)
	s_mov_b32 m0, s44
	v_mfma_f32_16x16x32_bf16 v[48:51], v[214:217], v[166:169], v[48:51]
	global_load_lds_dwordx4 v146, s[48:49]
	s_waitcnt lgkmcnt(1)
	v_mfma_f32_16x16x32_bf16 v[174:177], v[218:221], v[166:169], v[174:177]
	ds_read_b128 v[166:169], v6 offset:9216
	v_mfma_f32_16x16x32_bf16 v[64:67], v[214:217], v[178:181], v[64:67]
	v_mfma_f32_16x16x32_bf16 v[170:173], v[218:221], v[178:181], v[170:173]
	ds_read_b128 v[178:181], v6 offset:11264
	v_mfma_f32_16x16x32_bf16 v[80:83], v[214:217], v[222:225], v[80:83]
	v_mfma_f32_16x16x32_bf16 v[32:35], v[218:221], v[222:225], v[32:35]
	ds_read_b128 v[222:225], v6 offset:13312
	s_waitcnt lgkmcnt(3)
	v_mfma_f32_16x16x32_bf16 v[88:91], v[158:161], v[226:229], v[88:91]
	v_mfma_f32_16x16x32_bf16 v[92:95], v[162:165], v[226:229], v[92:95]
	v_mfma_f32_16x16x32_bf16 v[96:99], v[214:217], v[226:229], v[96:99]
	v_mfma_f32_16x16x32_bf16 v[36:39], v[218:221], v[226:229], v[36:39]
	ds_read_b128 v[226:229], v6 offset:15360
	s_waitcnt lgkmcnt(3)
	v_mfma_f32_16x16x32_bf16 v[104:107], v[158:161], v[166:169], v[104:107]
	v_mfma_f32_16x16x32_bf16 v[108:111], v[162:165], v[166:169], v[108:111]
	v_mfma_f32_16x16x32_bf16 v[112:115], v[214:217], v[166:169], v[112:115]
	v_mfma_f32_16x16x32_bf16 v[52:55], v[218:221], v[166:169], v[52:55]
	s_waitcnt lgkmcnt(2)
	v_mfma_f32_16x16x32_bf16 v[116:119], v[158:161], v[178:181], v[116:119]
	v_mfma_f32_16x16x32_bf16 v[120:123], v[162:165], v[178:181], v[120:123]
	v_mfma_f32_16x16x32_bf16 v[124:127], v[214:217], v[178:181], v[124:127]
	v_mfma_f32_16x16x32_bf16 v[68:71], v[218:221], v[178:181], v[68:71]
	s_waitcnt lgkmcnt(1)
	v_mfma_f32_16x16x32_bf16 v[128:131], v[158:161], v[222:225], v[128:131]
	v_mfma_f32_16x16x32_bf16 v[132:135], v[162:165], v[222:225], v[132:135]
	v_mfma_f32_16x16x32_bf16 v[136:139], v[214:217], v[222:225], v[136:139]
	v_mfma_f32_16x16x32_bf16 v[84:87], v[218:221], v[222:225], v[84:87]
	s_waitcnt lgkmcnt(0)
	v_mfma_f32_16x16x32_bf16 v[100:103], v[158:161], v[226:229], v[100:103]
	v_mfma_f32_16x16x32_bf16 v[140:143], v[162:165], v[226:229], v[140:143]
	v_mfma_f32_16x16x32_bf16 v[150:153], v[214:217], v[226:229], v[150:153]
	v_mfma_f32_16x16x32_bf16 v[154:157], v[218:221], v[226:229], v[154:157]
	s_add_u32 s46, s16, 0x300
	s_addc_u32 s47, s17, 0
	s_add_u32 s48, s18, 0x300
	s_waitcnt vmcnt(0)
	s_barrier
	s_addc_u32 s49, s19, 0
	ds_read_b128 v[158:161], v8
	ds_read_b128 v[162:165], v12
	ds_read_b128 v[166:169], v9
	ds_read_b128 v[178:181], v13
	ds_read_b128 v[214:217], v11
	ds_read_b128 v[218:221], v10
	ds_read_b128 v[222:225], v14
	ds_read_b128 v[226:229], v15
	s_waitcnt lgkmcnt(6)
	v_mfma_f32_16x16x32_bf16 v[40:43], v[158:161], v[162:165], v[40:43]
	s_waitcnt lgkmcnt(5)
	v_mfma_f32_16x16x32_bf16 v[44:47], v[166:169], v[162:165], v[44:47]
	s_waitcnt lgkmcnt(4)
	v_mfma_f32_16x16x32_bf16 v[56:59], v[158:161], v[178:181], v[56:59]
	s_mov_b32 m0, s1
	v_mfma_f32_16x16x32_bf16 v[60:63], v[166:169], v[178:181], v[60:63]
	global_load_lds_dwordx4 v0, s[46:47]
	s_waitcnt lgkmcnt(3)
	v_mfma_f32_16x16x32_bf16 v[48:51], v[214:217], v[162:165], v[48:51]
	v_mfma_f32_16x16x32_bf16 v[64:67], v[214:217], v[178:181], v[64:67]
	s_waitcnt lgkmcnt(2)
	v_mfma_f32_16x16x32_bf16 v[174:177], v[218:221], v[162:165], v[174:177]
	ds_read_b128 v[162:165], v16
	v_mfma_f32_16x16x32_bf16 v[170:173], v[218:221], v[178:181], v[170:173]
	ds_read_b128 v[178:181], v17
	s_waitcnt lgkmcnt(3)
	s_mov_b32 m0, s30
	v_mfma_f32_16x16x32_bf16 v[72:75], v[158:161], v[222:225], v[72:75]
	global_load_lds_dwordx4 v0, s[48:49]
	v_mfma_f32_16x16x32_bf16 v[76:79], v[166:169], v[222:225], v[76:79]
	v_mfma_f32_16x16x32_bf16 v[80:83], v[214:217], v[222:225], v[80:83]
	v_mfma_f32_16x16x32_bf16 v[32:35], v[218:221], v[222:225], v[32:35]
	ds_read_b128 v[222:225], v18
	s_waitcnt lgkmcnt(3)
	v_mfma_f32_16x16x32_bf16 v[88:91], v[158:161], v[226:229], v[88:91]
	s_mov_b32 m0, s31
	v_mfma_f32_16x16x32_bf16 v[92:95], v[166:169], v[226:229], v[92:95]
	global_load_lds_dwordx4 v2, s[46:47]
	v_mfma_f32_16x16x32_bf16 v[96:99], v[214:217], v[226:229], v[96:99]
	v_mfma_f32_16x16x32_bf16 v[36:39], v[218:221], v[226:229], v[36:39]
	ds_read_b128 v[226:229], v19
	s_waitcnt lgkmcnt(3)
	v_mfma_f32_16x16x32_bf16 v[104:107], v[158:161], v[162:165], v[104:107]
	s_waitcnt lgkmcnt(2)
	v_mfma_f32_16x16x32_bf16 v[116:119], v[158:161], v[178:181], v[116:119]
	s_waitcnt lgkmcnt(1)
	s_mov_b32 m0, s34
	v_mfma_f32_16x16x32_bf16 v[128:131], v[158:161], v[222:225], v[128:131]
	global_load_lds_dwordx4 v2, s[48:49]
	s_waitcnt lgkmcnt(0)
	v_mfma_f32_16x16x32_bf16 v[100:103], v[158:161], v[226:229], v[100:103]
	ds_read_b128 v[158:161], v20
	v_mfma_f32_16x16x32_bf16 v[108:111], v[166:169], v[162:165], v[108:111]
	v_mfma_f32_16x16x32_bf16 v[120:123], v[166:169], v[178:181], v[120:123]
	v_mfma_f32_16x16x32_bf16 v[132:135], v[166:169], v[222:225], v[132:135]
	s_mov_b32 m0, s35
	v_mfma_f32_16x16x32_bf16 v[140:143], v[166:169], v[226:229], v[140:143]
	global_load_lds_dwordx4 v4, s[46:47]
	ds_read_b128 v[166:169], v24
	v_mfma_f32_16x16x32_bf16 v[112:115], v[214:217], v[162:165], v[112:115]
	v_mfma_f32_16x16x32_bf16 v[52:55], v[218:221], v[162:165], v[52:55]
	ds_read_b128 v[162:165], v21
	v_mfma_f32_16x16x32_bf16 v[124:127], v[214:217], v[178:181], v[124:127]
	v_mfma_f32_16x16x32_bf16 v[68:71], v[218:221], v[178:181], v[68:71]
	ds_read_b128 v[178:181], v25
	s_mov_b32 m0, s36
	v_mfma_f32_16x16x32_bf16 v[136:139], v[214:217], v[222:225], v[136:139]
	global_load_lds_dwordx4 v4, s[48:49]
	v_mfma_f32_16x16x32_bf16 v[84:87], v[218:221], v[222:225], v[84:87]
	ds_read_b128 v[222:225], v26
	v_mfma_f32_16x16x32_bf16 v[150:153], v[214:217], v[226:229], v[150:153]
	ds_read_b128 v[214:217], v23
	v_mfma_f32_16x16x32_bf16 v[154:157], v[218:221], v[226:229], v[154:157]
	ds_read_b128 v[218:221], v22
	ds_read_b128 v[226:229], v27
	s_waitcnt lgkmcnt(6)
	v_mfma_f32_16x16x32_bf16 v[40:43], v[158:161], v[166:169], v[40:43]
	s_waitcnt lgkmcnt(5)
	s_mov_b32 m0, s37
	v_mfma_f32_16x16x32_bf16 v[44:47], v[162:165], v[166:169], v[44:47]
	global_load_lds_dwordx4 v146, s[46:47]
	s_waitcnt lgkmcnt(4)
	v_mfma_f32_16x16x32_bf16 v[56:59], v[158:161], v[178:181], v[56:59]
	v_mfma_f32_16x16x32_bf16 v[60:63], v[162:165], v[178:181], v[60:63]
	s_waitcnt lgkmcnt(3)
	v_mfma_f32_16x16x32_bf16 v[72:75], v[158:161], v[222:225], v[72:75]
	v_mfma_f32_16x16x32_bf16 v[76:79], v[162:165], v[222:225], v[76:79]
	s_waitcnt lgkmcnt(2)
	s_mov_b32 m0, s38
	v_mfma_f32_16x16x32_bf16 v[48:51], v[214:217], v[166:169], v[48:51]
	global_load_lds_dwordx4 v146, s[48:49]
	s_waitcnt lgkmcnt(1)
	v_mfma_f32_16x16x32_bf16 v[174:177], v[218:221], v[166:169], v[174:177]
	ds_read_b128 v[166:169], v28
	v_mfma_f32_16x16x32_bf16 v[64:67], v[214:217], v[178:181], v[64:67]
	v_mfma_f32_16x16x32_bf16 v[170:173], v[218:221], v[178:181], v[170:173]
	ds_read_b128 v[178:181], v29
	v_mfma_f32_16x16x32_bf16 v[80:83], v[214:217], v[222:225], v[80:83]
	v_mfma_f32_16x16x32_bf16 v[32:35], v[218:221], v[222:225], v[32:35]
	ds_read_b128 v[222:225], v30
	s_waitcnt lgkmcnt(3)
	v_mfma_f32_16x16x32_bf16 v[88:91], v[158:161], v[226:229], v[88:91]
	v_mfma_f32_16x16x32_bf16 v[92:95], v[162:165], v[226:229], v[92:95]
	v_mfma_f32_16x16x32_bf16 v[96:99], v[214:217], v[226:229], v[96:99]
	v_mfma_f32_16x16x32_bf16 v[36:39], v[218:221], v[226:229], v[36:39]
	ds_read_b128 v[226:229], v31
	s_waitcnt lgkmcnt(3)
	v_mfma_f32_16x16x32_bf16 v[104:107], v[158:161], v[166:169], v[104:107]
	v_mfma_f32_16x16x32_bf16 v[108:111], v[162:165], v[166:169], v[108:111]
	v_mfma_f32_16x16x32_bf16 v[112:115], v[214:217], v[166:169], v[112:115]
	v_mfma_f32_16x16x32_bf16 v[52:55], v[218:221], v[166:169], v[52:55]
	s_waitcnt lgkmcnt(2)
	v_mfma_f32_16x16x32_bf16 v[116:119], v[158:161], v[178:181], v[116:119]
	v_mfma_f32_16x16x32_bf16 v[120:123], v[162:165], v[178:181], v[120:123]
	v_mfma_f32_16x16x32_bf16 v[124:127], v[214:217], v[178:181], v[124:127]
	v_mfma_f32_16x16x32_bf16 v[68:71], v[218:221], v[178:181], v[68:71]
	s_waitcnt lgkmcnt(1)
	v_mfma_f32_16x16x32_bf16 v[128:131], v[158:161], v[222:225], v[128:131]
	v_mfma_f32_16x16x32_bf16 v[132:135], v[162:165], v[222:225], v[132:135]
	v_mfma_f32_16x16x32_bf16 v[136:139], v[214:217], v[222:225], v[136:139]
	v_mfma_f32_16x16x32_bf16 v[84:87], v[218:221], v[222:225], v[84:87]
	s_waitcnt lgkmcnt(0)
	v_mfma_f32_16x16x32_bf16 v[100:103], v[158:161], v[226:229], v[100:103]
	v_mfma_f32_16x16x32_bf16 v[140:143], v[162:165], v[226:229], v[140:143]
	v_mfma_f32_16x16x32_bf16 v[150:153], v[214:217], v[226:229], v[150:153]
	v_mfma_f32_16x16x32_bf16 v[154:157], v[218:221], v[226:229], v[154:157]
	s_add_u32 s46, s16, 0x380
	s_addc_u32 s47, s17, 0
	s_add_u32 s48, s18, 0x380
	s_waitcnt vmcnt(0)
	s_barrier
	s_addc_u32 s49, s19, 0
	ds_read_b128 v[158:161], v7 offset:32768
	ds_read_b128 v[162:165], v6
	ds_read_b128 v[166:169], v7 offset:34816
	ds_read_b128 v[178:181], v6 offset:2048
	ds_read_b128 v[214:217], v7 offset:36864
	ds_read_b128 v[218:221], v7 offset:38912
	ds_read_b128 v[222:225], v6 offset:4096
	ds_read_b128 v[226:229], v6 offset:6144
	s_waitcnt lgkmcnt(6)
	v_mfma_f32_16x16x32_bf16 v[40:43], v[158:161], v[162:165], v[40:43]
	s_waitcnt lgkmcnt(5)
	v_mfma_f32_16x16x32_bf16 v[44:47], v[166:169], v[162:165], v[44:47]
	s_waitcnt lgkmcnt(4)
	v_mfma_f32_16x16x32_bf16 v[56:59], v[158:161], v[178:181], v[56:59]
	s_mov_b32 m0, s25
	v_mfma_f32_16x16x32_bf16 v[60:63], v[166:169], v[178:181], v[60:63]
	global_load_lds_dwordx4 v0, s[46:47]
	s_waitcnt lgkmcnt(3)
	v_mfma_f32_16x16x32_bf16 v[48:51], v[214:217], v[162:165], v[48:51]
	v_mfma_f32_16x16x32_bf16 v[64:67], v[214:217], v[178:181], v[64:67]
	s_waitcnt lgkmcnt(2)
	v_mfma_f32_16x16x32_bf16 v[174:177], v[218:221], v[162:165], v[174:177]
	ds_read_b128 v[162:165], v6 offset:8192
	v_mfma_f32_16x16x32_bf16 v[170:173], v[218:221], v[178:181], v[170:173]
	ds_read_b128 v[178:181], v6 offset:10240
	s_waitcnt lgkmcnt(3)
	s_mov_b32 m0, s24
	v_mfma_f32_16x16x32_bf16 v[72:75], v[158:161], v[222:225], v[72:75]
	global_load_lds_dwordx4 v0, s[48:49]
	v_mfma_f32_16x16x32_bf16 v[76:79], v[166:169], v[222:225], v[76:79]
	v_mfma_f32_16x16x32_bf16 v[80:83], v[214:217], v[222:225], v[80:83]
	v_mfma_f32_16x16x32_bf16 v[32:35], v[218:221], v[222:225], v[32:35]
	ds_read_b128 v[222:225], v6 offset:12288
	s_waitcnt lgkmcnt(3)
	v_mfma_f32_16x16x32_bf16 v[88:91], v[158:161], v[226:229], v[88:91]
	s_mov_b32 m0, s39
	v_mfma_f32_16x16x32_bf16 v[92:95], v[166:169], v[226:229], v[92:95]
	global_load_lds_dwordx4 v2, s[46:47]
	v_mfma_f32_16x16x32_bf16 v[96:99], v[214:217], v[226:229], v[96:99]
	v_mfma_f32_16x16x32_bf16 v[36:39], v[218:221], v[226:229], v[36:39]
	ds_read_b128 v[226:229], v6 offset:14336
	s_waitcnt lgkmcnt(3)
	v_mfma_f32_16x16x32_bf16 v[104:107], v[158:161], v[162:165], v[104:107]
	s_waitcnt lgkmcnt(2)
	v_mfma_f32_16x16x32_bf16 v[116:119], v[158:161], v[178:181], v[116:119]
	s_waitcnt lgkmcnt(1)
	s_mov_b32 m0, s40
	v_mfma_f32_16x16x32_bf16 v[128:131], v[158:161], v[222:225], v[128:131]
	global_load_lds_dwordx4 v2, s[48:49]
	s_waitcnt lgkmcnt(0)
	v_mfma_f32_16x16x32_bf16 v[100:103], v[158:161], v[226:229], v[100:103]
	ds_read_b128 v[158:161], v7 offset:33792
	v_mfma_f32_16x16x32_bf16 v[108:111], v[166:169], v[162:165], v[108:111]
	v_mfma_f32_16x16x32_bf16 v[120:123], v[166:169], v[178:181], v[120:123]
	v_mfma_f32_16x16x32_bf16 v[132:135], v[166:169], v[222:225], v[132:135]
	s_mov_b32 m0, s41
	v_mfma_f32_16x16x32_bf16 v[140:143], v[166:169], v[226:229], v[140:143]
	global_load_lds_dwordx4 v4, s[46:47]
	ds_read_b128 v[166:169], v6 offset:1024
	v_mfma_f32_16x16x32_bf16 v[112:115], v[214:217], v[162:165], v[112:115]
	v_mfma_f32_16x16x32_bf16 v[52:55], v[218:221], v[162:165], v[52:55]
	ds_read_b128 v[162:165], v7 offset:35840
	v_mfma_f32_16x16x32_bf16 v[124:127], v[214:217], v[178:181], v[124:127]
	v_mfma_f32_16x16x32_bf16 v[68:71], v[218:221], v[178:181], v[68:71]
	ds_read_b128 v[178:181], v6 offset:3072
	s_mov_b32 m0, s42
	v_mfma_f32_16x16x32_bf16 v[136:139], v[214:217], v[222:225], v[136:139]
	global_load_lds_dwordx4 v4, s[48:49]
	v_mfma_f32_16x16x32_bf16 v[84:87], v[218:221], v[222:225], v[84:87]
	ds_read_b128 v[222:225], v6 offset:5120
	v_mfma_f32_16x16x32_bf16 v[150:153], v[214:217], v[226:229], v[150:153]
	ds_read_b128 v[214:217], v7 offset:37888
	v_mfma_f32_16x16x32_bf16 v[154:157], v[218:221], v[226:229], v[154:157]
	ds_read_b128 v[218:221], v7 offset:39936
	ds_read_b128 v[226:229], v6 offset:7168
	s_waitcnt lgkmcnt(6)
	v_mfma_f32_16x16x32_bf16 v[40:43], v[158:161], v[166:169], v[40:43]
	s_waitcnt lgkmcnt(5)
	s_mov_b32 m0, s43
	v_mfma_f32_16x16x32_bf16 v[44:47], v[162:165], v[166:169], v[44:47]
	global_load_lds_dwordx4 v146, s[46:47]
	s_waitcnt lgkmcnt(4)
	v_mfma_f32_16x16x32_bf16 v[56:59], v[158:161], v[178:181], v[56:59]
	v_mfma_f32_16x16x32_bf16 v[60:63], v[162:165], v[178:181], v[60:63]
	s_waitcnt lgkmcnt(3)
	v_mfma_f32_16x16x32_bf16 v[72:75], v[158:161], v[222:225], v[72:75]
	v_mfma_f32_16x16x32_bf16 v[76:79], v[162:165], v[222:225], v[76:79]
	s_waitcnt lgkmcnt(2)
	s_mov_b32 m0, s44
	v_mfma_f32_16x16x32_bf16 v[48:51], v[214:217], v[166:169], v[48:51]
	global_load_lds_dwordx4 v146, s[48:49]
	s_waitcnt lgkmcnt(1)
	v_mfma_f32_16x16x32_bf16 v[174:177], v[218:221], v[166:169], v[174:177]
	ds_read_b128 v[166:169], v6 offset:9216
	v_mfma_f32_16x16x32_bf16 v[64:67], v[214:217], v[178:181], v[64:67]
	v_mfma_f32_16x16x32_bf16 v[170:173], v[218:221], v[178:181], v[170:173]
	ds_read_b128 v[178:181], v6 offset:11264
	v_mfma_f32_16x16x32_bf16 v[80:83], v[214:217], v[222:225], v[80:83]
	v_mfma_f32_16x16x32_bf16 v[32:35], v[218:221], v[222:225], v[32:35]
	ds_read_b128 v[222:225], v6 offset:13312
	s_waitcnt lgkmcnt(3)
	v_mfma_f32_16x16x32_bf16 v[88:91], v[158:161], v[226:229], v[88:91]
	v_mfma_f32_16x16x32_bf16 v[92:95], v[162:165], v[226:229], v[92:95]
	v_mfma_f32_16x16x32_bf16 v[96:99], v[214:217], v[226:229], v[96:99]
	v_mfma_f32_16x16x32_bf16 v[36:39], v[218:221], v[226:229], v[36:39]
	ds_read_b128 v[226:229], v6 offset:15360
	s_waitcnt lgkmcnt(3)
	v_mfma_f32_16x16x32_bf16 v[104:107], v[158:161], v[166:169], v[104:107]
	v_mfma_f32_16x16x32_bf16 v[108:111], v[162:165], v[166:169], v[108:111]
	v_mfma_f32_16x16x32_bf16 v[112:115], v[214:217], v[166:169], v[112:115]
	v_mfma_f32_16x16x32_bf16 v[52:55], v[218:221], v[166:169], v[52:55]
	s_waitcnt lgkmcnt(2)
	v_mfma_f32_16x16x32_bf16 v[116:119], v[158:161], v[178:181], v[116:119]
	v_mfma_f32_16x16x32_bf16 v[120:123], v[162:165], v[178:181], v[120:123]
	v_mfma_f32_16x16x32_bf16 v[124:127], v[214:217], v[178:181], v[124:127]
	v_mfma_f32_16x16x32_bf16 v[68:71], v[218:221], v[178:181], v[68:71]
	s_waitcnt lgkmcnt(1)
	v_mfma_f32_16x16x32_bf16 v[128:131], v[158:161], v[222:225], v[128:131]
	v_mfma_f32_16x16x32_bf16 v[132:135], v[162:165], v[222:225], v[132:135]
	v_mfma_f32_16x16x32_bf16 v[136:139], v[214:217], v[222:225], v[136:139]
	v_mfma_f32_16x16x32_bf16 v[84:87], v[218:221], v[222:225], v[84:87]
	s_waitcnt lgkmcnt(0)
	v_mfma_f32_16x16x32_bf16 v[100:103], v[158:161], v[226:229], v[100:103]
	v_mfma_f32_16x16x32_bf16 v[140:143], v[162:165], v[226:229], v[140:143]
	v_mfma_f32_16x16x32_bf16 v[150:153], v[214:217], v[226:229], v[150:153]
	v_mfma_f32_16x16x32_bf16 v[154:157], v[218:221], v[226:229], v[154:157]
	s_add_u32 s46, s16, 0x400
	s_addc_u32 s47, s17, 0
	s_add_u32 s48, s18, 0x400
	s_waitcnt vmcnt(0)
	s_barrier
	s_addc_u32 s49, s19, 0
	ds_read_b128 v[158:161], v8
	ds_read_b128 v[162:165], v12
	ds_read_b128 v[166:169], v9
	ds_read_b128 v[178:181], v13
	ds_read_b128 v[214:217], v11
	ds_read_b128 v[218:221], v10
	ds_read_b128 v[222:225], v14
	ds_read_b128 v[226:229], v15
	s_waitcnt lgkmcnt(6)
	v_mfma_f32_16x16x32_bf16 v[40:43], v[158:161], v[162:165], v[40:43]
	s_waitcnt lgkmcnt(5)
	v_mfma_f32_16x16x32_bf16 v[44:47], v[166:169], v[162:165], v[44:47]
	s_waitcnt lgkmcnt(4)
	v_mfma_f32_16x16x32_bf16 v[56:59], v[158:161], v[178:181], v[56:59]
	s_mov_b32 m0, s1
	v_mfma_f32_16x16x32_bf16 v[60:63], v[166:169], v[178:181], v[60:63]
	global_load_lds_dwordx4 v0, s[46:47]
	s_waitcnt lgkmcnt(3)
	v_mfma_f32_16x16x32_bf16 v[48:51], v[214:217], v[162:165], v[48:51]
	v_mfma_f32_16x16x32_bf16 v[64:67], v[214:217], v[178:181], v[64:67]
	s_waitcnt lgkmcnt(2)
	v_mfma_f32_16x16x32_bf16 v[174:177], v[218:221], v[162:165], v[174:177]
	ds_read_b128 v[162:165], v16
	v_mfma_f32_16x16x32_bf16 v[170:173], v[218:221], v[178:181], v[170:173]
	ds_read_b128 v[178:181], v17
	s_waitcnt lgkmcnt(3)
	s_mov_b32 m0, s30
	v_mfma_f32_16x16x32_bf16 v[72:75], v[158:161], v[222:225], v[72:75]
	global_load_lds_dwordx4 v0, s[48:49]
	v_mfma_f32_16x16x32_bf16 v[76:79], v[166:169], v[222:225], v[76:79]
	v_mfma_f32_16x16x32_bf16 v[80:83], v[214:217], v[222:225], v[80:83]
	v_mfma_f32_16x16x32_bf16 v[32:35], v[218:221], v[222:225], v[32:35]
	ds_read_b128 v[222:225], v18
	s_waitcnt lgkmcnt(3)
	v_mfma_f32_16x16x32_bf16 v[88:91], v[158:161], v[226:229], v[88:91]
	s_mov_b32 m0, s31
	v_mfma_f32_16x16x32_bf16 v[92:95], v[166:169], v[226:229], v[92:95]
	global_load_lds_dwordx4 v2, s[46:47]
	v_mfma_f32_16x16x32_bf16 v[96:99], v[214:217], v[226:229], v[96:99]
	v_mfma_f32_16x16x32_bf16 v[36:39], v[218:221], v[226:229], v[36:39]
	ds_read_b128 v[226:229], v19
	s_waitcnt lgkmcnt(3)
	v_mfma_f32_16x16x32_bf16 v[104:107], v[158:161], v[162:165], v[104:107]
	s_waitcnt lgkmcnt(2)
	v_mfma_f32_16x16x32_bf16 v[116:119], v[158:161], v[178:181], v[116:119]
	s_waitcnt lgkmcnt(1)
	s_mov_b32 m0, s34
	v_mfma_f32_16x16x32_bf16 v[128:131], v[158:161], v[222:225], v[128:131]
	global_load_lds_dwordx4 v2, s[48:49]
	s_waitcnt lgkmcnt(0)
	v_mfma_f32_16x16x32_bf16 v[100:103], v[158:161], v[226:229], v[100:103]
	ds_read_b128 v[158:161], v20
	v_mfma_f32_16x16x32_bf16 v[108:111], v[166:169], v[162:165], v[108:111]
	v_mfma_f32_16x16x32_bf16 v[120:123], v[166:169], v[178:181], v[120:123]
	v_mfma_f32_16x16x32_bf16 v[132:135], v[166:169], v[222:225], v[132:135]
	s_mov_b32 m0, s35
	v_mfma_f32_16x16x32_bf16 v[140:143], v[166:169], v[226:229], v[140:143]
	global_load_lds_dwordx4 v4, s[46:47]
	ds_read_b128 v[166:169], v24
	v_mfma_f32_16x16x32_bf16 v[112:115], v[214:217], v[162:165], v[112:115]
	v_mfma_f32_16x16x32_bf16 v[52:55], v[218:221], v[162:165], v[52:55]
	ds_read_b128 v[162:165], v21
	v_mfma_f32_16x16x32_bf16 v[124:127], v[214:217], v[178:181], v[124:127]
	v_mfma_f32_16x16x32_bf16 v[68:71], v[218:221], v[178:181], v[68:71]
	ds_read_b128 v[178:181], v25
	s_mov_b32 m0, s36
	v_mfma_f32_16x16x32_bf16 v[136:139], v[214:217], v[222:225], v[136:139]
	global_load_lds_dwordx4 v4, s[48:49]
	v_mfma_f32_16x16x32_bf16 v[84:87], v[218:221], v[222:225], v[84:87]
	ds_read_b128 v[222:225], v26
	v_mfma_f32_16x16x32_bf16 v[150:153], v[214:217], v[226:229], v[150:153]
	ds_read_b128 v[214:217], v23
	v_mfma_f32_16x16x32_bf16 v[154:157], v[218:221], v[226:229], v[154:157]
	ds_read_b128 v[218:221], v22
	ds_read_b128 v[226:229], v27
	s_waitcnt lgkmcnt(6)
	v_mfma_f32_16x16x32_bf16 v[40:43], v[158:161], v[166:169], v[40:43]
	s_waitcnt lgkmcnt(5)
	s_mov_b32 m0, s37
	v_mfma_f32_16x16x32_bf16 v[44:47], v[162:165], v[166:169], v[44:47]
	global_load_lds_dwordx4 v146, s[46:47]
	s_waitcnt lgkmcnt(4)
	v_mfma_f32_16x16x32_bf16 v[56:59], v[158:161], v[178:181], v[56:59]
	v_mfma_f32_16x16x32_bf16 v[60:63], v[162:165], v[178:181], v[60:63]
	s_waitcnt lgkmcnt(3)
	v_mfma_f32_16x16x32_bf16 v[72:75], v[158:161], v[222:225], v[72:75]
	v_mfma_f32_16x16x32_bf16 v[76:79], v[162:165], v[222:225], v[76:79]
	s_waitcnt lgkmcnt(2)
	s_mov_b32 m0, s38
	v_mfma_f32_16x16x32_bf16 v[48:51], v[214:217], v[166:169], v[48:51]
	global_load_lds_dwordx4 v146, s[48:49]
	s_waitcnt lgkmcnt(1)
	v_mfma_f32_16x16x32_bf16 v[174:177], v[218:221], v[166:169], v[174:177]
	ds_read_b128 v[166:169], v28
	v_mfma_f32_16x16x32_bf16 v[64:67], v[214:217], v[178:181], v[64:67]
	v_mfma_f32_16x16x32_bf16 v[170:173], v[218:221], v[178:181], v[170:173]
	ds_read_b128 v[178:181], v29
	v_mfma_f32_16x16x32_bf16 v[80:83], v[214:217], v[222:225], v[80:83]
	v_mfma_f32_16x16x32_bf16 v[32:35], v[218:221], v[222:225], v[32:35]
	ds_read_b128 v[222:225], v30
	s_waitcnt lgkmcnt(3)
	v_mfma_f32_16x16x32_bf16 v[88:91], v[158:161], v[226:229], v[88:91]
	v_mfma_f32_16x16x32_bf16 v[92:95], v[162:165], v[226:229], v[92:95]
	v_mfma_f32_16x16x32_bf16 v[96:99], v[214:217], v[226:229], v[96:99]
	v_mfma_f32_16x16x32_bf16 v[36:39], v[218:221], v[226:229], v[36:39]
	ds_read_b128 v[226:229], v31
	s_waitcnt lgkmcnt(3)
	v_mfma_f32_16x16x32_bf16 v[104:107], v[158:161], v[166:169], v[104:107]
	v_mfma_f32_16x16x32_bf16 v[108:111], v[162:165], v[166:169], v[108:111]
	v_mfma_f32_16x16x32_bf16 v[112:115], v[214:217], v[166:169], v[112:115]
	v_mfma_f32_16x16x32_bf16 v[52:55], v[218:221], v[166:169], v[52:55]
	s_waitcnt lgkmcnt(2)
	v_mfma_f32_16x16x32_bf16 v[116:119], v[158:161], v[178:181], v[116:119]
	v_mfma_f32_16x16x32_bf16 v[120:123], v[162:165], v[178:181], v[120:123]
	v_mfma_f32_16x16x32_bf16 v[124:127], v[214:217], v[178:181], v[124:127]
	v_mfma_f32_16x16x32_bf16 v[68:71], v[218:221], v[178:181], v[68:71]
	s_waitcnt lgkmcnt(1)
	v_mfma_f32_16x16x32_bf16 v[128:131], v[158:161], v[222:225], v[128:131]
	v_mfma_f32_16x16x32_bf16 v[132:135], v[162:165], v[222:225], v[132:135]
	v_mfma_f32_16x16x32_bf16 v[136:139], v[214:217], v[222:225], v[136:139]
	v_mfma_f32_16x16x32_bf16 v[84:87], v[218:221], v[222:225], v[84:87]
	s_waitcnt lgkmcnt(0)
	v_mfma_f32_16x16x32_bf16 v[100:103], v[158:161], v[226:229], v[100:103]
	v_mfma_f32_16x16x32_bf16 v[140:143], v[162:165], v[226:229], v[140:143]
	v_mfma_f32_16x16x32_bf16 v[150:153], v[214:217], v[226:229], v[150:153]
	v_mfma_f32_16x16x32_bf16 v[154:157], v[218:221], v[226:229], v[154:157]
	s_add_u32 s46, s16, 0x480
	s_addc_u32 s47, s17, 0
	s_add_u32 s48, s18, 0x480
	s_waitcnt vmcnt(0)
	s_barrier
	s_addc_u32 s49, s19, 0
	ds_read_b128 v[158:161], v7 offset:32768
	ds_read_b128 v[162:165], v6
	ds_read_b128 v[166:169], v7 offset:34816
	ds_read_b128 v[178:181], v6 offset:2048
	ds_read_b128 v[214:217], v7 offset:36864
	ds_read_b128 v[218:221], v7 offset:38912
	ds_read_b128 v[222:225], v6 offset:4096
	ds_read_b128 v[226:229], v6 offset:6144
	s_waitcnt lgkmcnt(6)
	v_mfma_f32_16x16x32_bf16 v[40:43], v[158:161], v[162:165], v[40:43]
	s_waitcnt lgkmcnt(5)
	v_mfma_f32_16x16x32_bf16 v[44:47], v[166:169], v[162:165], v[44:47]
	s_waitcnt lgkmcnt(4)
	v_mfma_f32_16x16x32_bf16 v[56:59], v[158:161], v[178:181], v[56:59]
	s_mov_b32 m0, s25
	v_mfma_f32_16x16x32_bf16 v[60:63], v[166:169], v[178:181], v[60:63]
	global_load_lds_dwordx4 v0, s[46:47]
	s_waitcnt lgkmcnt(3)
	v_mfma_f32_16x16x32_bf16 v[48:51], v[214:217], v[162:165], v[48:51]
	v_mfma_f32_16x16x32_bf16 v[64:67], v[214:217], v[178:181], v[64:67]
	s_waitcnt lgkmcnt(2)
	v_mfma_f32_16x16x32_bf16 v[174:177], v[218:221], v[162:165], v[174:177]
	ds_read_b128 v[162:165], v6 offset:8192
	v_mfma_f32_16x16x32_bf16 v[170:173], v[218:221], v[178:181], v[170:173]
	ds_read_b128 v[178:181], v6 offset:10240
	s_waitcnt lgkmcnt(3)
	s_mov_b32 m0, s24
	v_mfma_f32_16x16x32_bf16 v[72:75], v[158:161], v[222:225], v[72:75]
	global_load_lds_dwordx4 v0, s[48:49]
	v_mfma_f32_16x16x32_bf16 v[76:79], v[166:169], v[222:225], v[76:79]
	v_mfma_f32_16x16x32_bf16 v[80:83], v[214:217], v[222:225], v[80:83]
	v_mfma_f32_16x16x32_bf16 v[32:35], v[218:221], v[222:225], v[32:35]
	ds_read_b128 v[222:225], v6 offset:12288
	s_waitcnt lgkmcnt(3)
	v_mfma_f32_16x16x32_bf16 v[88:91], v[158:161], v[226:229], v[88:91]
	s_mov_b32 m0, s39
	v_mfma_f32_16x16x32_bf16 v[92:95], v[166:169], v[226:229], v[92:95]
	global_load_lds_dwordx4 v2, s[46:47]
	v_mfma_f32_16x16x32_bf16 v[96:99], v[214:217], v[226:229], v[96:99]
	v_mfma_f32_16x16x32_bf16 v[36:39], v[218:221], v[226:229], v[36:39]
	ds_read_b128 v[226:229], v6 offset:14336
	s_waitcnt lgkmcnt(3)
	v_mfma_f32_16x16x32_bf16 v[104:107], v[158:161], v[162:165], v[104:107]
	s_waitcnt lgkmcnt(2)
	v_mfma_f32_16x16x32_bf16 v[116:119], v[158:161], v[178:181], v[116:119]
	s_waitcnt lgkmcnt(1)
	s_mov_b32 m0, s40
	v_mfma_f32_16x16x32_bf16 v[128:131], v[158:161], v[222:225], v[128:131]
	global_load_lds_dwordx4 v2, s[48:49]
	s_waitcnt lgkmcnt(0)
	v_mfma_f32_16x16x32_bf16 v[100:103], v[158:161], v[226:229], v[100:103]
	ds_read_b128 v[158:161], v7 offset:33792
	v_mfma_f32_16x16x32_bf16 v[108:111], v[166:169], v[162:165], v[108:111]
	v_mfma_f32_16x16x32_bf16 v[120:123], v[166:169], v[178:181], v[120:123]
	v_mfma_f32_16x16x32_bf16 v[132:135], v[166:169], v[222:225], v[132:135]
	s_mov_b32 m0, s41
	v_mfma_f32_16x16x32_bf16 v[140:143], v[166:169], v[226:229], v[140:143]
	global_load_lds_dwordx4 v4, s[46:47]
	ds_read_b128 v[166:169], v6 offset:1024
	v_mfma_f32_16x16x32_bf16 v[112:115], v[214:217], v[162:165], v[112:115]
	v_mfma_f32_16x16x32_bf16 v[52:55], v[218:221], v[162:165], v[52:55]
	ds_read_b128 v[162:165], v7 offset:35840
	v_mfma_f32_16x16x32_bf16 v[124:127], v[214:217], v[178:181], v[124:127]
	v_mfma_f32_16x16x32_bf16 v[68:71], v[218:221], v[178:181], v[68:71]
	ds_read_b128 v[178:181], v6 offset:3072
	s_mov_b32 m0, s42
	v_mfma_f32_16x16x32_bf16 v[136:139], v[214:217], v[222:225], v[136:139]
	global_load_lds_dwordx4 v4, s[48:49]
	v_mfma_f32_16x16x32_bf16 v[84:87], v[218:221], v[222:225], v[84:87]
	ds_read_b128 v[222:225], v6 offset:5120
	v_mfma_f32_16x16x32_bf16 v[150:153], v[214:217], v[226:229], v[150:153]
	ds_read_b128 v[214:217], v7 offset:37888
	v_mfma_f32_16x16x32_bf16 v[154:157], v[218:221], v[226:229], v[154:157]
	ds_read_b128 v[218:221], v7 offset:39936
	ds_read_b128 v[226:229], v6 offset:7168
	s_waitcnt lgkmcnt(6)
	v_mfma_f32_16x16x32_bf16 v[40:43], v[158:161], v[166:169], v[40:43]
	s_waitcnt lgkmcnt(5)
	s_mov_b32 m0, s43
	v_mfma_f32_16x16x32_bf16 v[44:47], v[162:165], v[166:169], v[44:47]
	global_load_lds_dwordx4 v146, s[46:47]
	s_waitcnt lgkmcnt(4)
	v_mfma_f32_16x16x32_bf16 v[56:59], v[158:161], v[178:181], v[56:59]
	v_mfma_f32_16x16x32_bf16 v[60:63], v[162:165], v[178:181], v[60:63]
	s_waitcnt lgkmcnt(3)
	v_mfma_f32_16x16x32_bf16 v[72:75], v[158:161], v[222:225], v[72:75]
	v_mfma_f32_16x16x32_bf16 v[76:79], v[162:165], v[222:225], v[76:79]
	s_waitcnt lgkmcnt(2)
	s_mov_b32 m0, s44
	v_mfma_f32_16x16x32_bf16 v[48:51], v[214:217], v[166:169], v[48:51]
	global_load_lds_dwordx4 v146, s[48:49]
	s_waitcnt lgkmcnt(1)
	v_mfma_f32_16x16x32_bf16 v[174:177], v[218:221], v[166:169], v[174:177]
	ds_read_b128 v[166:169], v6 offset:9216
	v_mfma_f32_16x16x32_bf16 v[64:67], v[214:217], v[178:181], v[64:67]
	v_mfma_f32_16x16x32_bf16 v[170:173], v[218:221], v[178:181], v[170:173]
	ds_read_b128 v[178:181], v6 offset:11264
	v_mfma_f32_16x16x32_bf16 v[80:83], v[214:217], v[222:225], v[80:83]
	v_mfma_f32_16x16x32_bf16 v[32:35], v[218:221], v[222:225], v[32:35]
	ds_read_b128 v[222:225], v6 offset:13312
	s_waitcnt lgkmcnt(3)
	v_mfma_f32_16x16x32_bf16 v[88:91], v[158:161], v[226:229], v[88:91]
	v_mfma_f32_16x16x32_bf16 v[92:95], v[162:165], v[226:229], v[92:95]
	v_mfma_f32_16x16x32_bf16 v[96:99], v[214:217], v[226:229], v[96:99]
	v_mfma_f32_16x16x32_bf16 v[36:39], v[218:221], v[226:229], v[36:39]
	ds_read_b128 v[226:229], v6 offset:15360
	s_waitcnt lgkmcnt(3)
	v_mfma_f32_16x16x32_bf16 v[104:107], v[158:161], v[166:169], v[104:107]
	v_mfma_f32_16x16x32_bf16 v[108:111], v[162:165], v[166:169], v[108:111]
	v_mfma_f32_16x16x32_bf16 v[112:115], v[214:217], v[166:169], v[112:115]
	v_mfma_f32_16x16x32_bf16 v[52:55], v[218:221], v[166:169], v[52:55]
	s_waitcnt lgkmcnt(2)
	v_mfma_f32_16x16x32_bf16 v[116:119], v[158:161], v[178:181], v[116:119]
	v_mfma_f32_16x16x32_bf16 v[120:123], v[162:165], v[178:181], v[120:123]
	v_mfma_f32_16x16x32_bf16 v[124:127], v[214:217], v[178:181], v[124:127]
	v_mfma_f32_16x16x32_bf16 v[68:71], v[218:221], v[178:181], v[68:71]
	s_waitcnt lgkmcnt(1)
	v_mfma_f32_16x16x32_bf16 v[128:131], v[158:161], v[222:225], v[128:131]
	v_mfma_f32_16x16x32_bf16 v[132:135], v[162:165], v[222:225], v[132:135]
	v_mfma_f32_16x16x32_bf16 v[136:139], v[214:217], v[222:225], v[136:139]
	v_mfma_f32_16x16x32_bf16 v[84:87], v[218:221], v[222:225], v[84:87]
	s_waitcnt lgkmcnt(0)
	v_mfma_f32_16x16x32_bf16 v[100:103], v[158:161], v[226:229], v[100:103]
	v_mfma_f32_16x16x32_bf16 v[140:143], v[162:165], v[226:229], v[140:143]
	v_mfma_f32_16x16x32_bf16 v[150:153], v[214:217], v[226:229], v[150:153]
	v_mfma_f32_16x16x32_bf16 v[154:157], v[218:221], v[226:229], v[154:157]
	s_add_u32 s46, s16, 0x500
	s_addc_u32 s47, s17, 0
	s_add_u32 s48, s18, 0x500
	s_waitcnt vmcnt(0)
	s_barrier
	s_addc_u32 s49, s19, 0
	ds_read_b128 v[158:161], v8
	ds_read_b128 v[162:165], v12
	ds_read_b128 v[166:169], v9
	ds_read_b128 v[178:181], v13
	ds_read_b128 v[214:217], v11
	ds_read_b128 v[218:221], v10
	ds_read_b128 v[222:225], v14
	ds_read_b128 v[226:229], v15
	s_waitcnt lgkmcnt(6)
	v_mfma_f32_16x16x32_bf16 v[40:43], v[158:161], v[162:165], v[40:43]
	s_waitcnt lgkmcnt(5)
	v_mfma_f32_16x16x32_bf16 v[44:47], v[166:169], v[162:165], v[44:47]
	s_waitcnt lgkmcnt(4)
	v_mfma_f32_16x16x32_bf16 v[56:59], v[158:161], v[178:181], v[56:59]
	s_mov_b32 m0, s1
	v_mfma_f32_16x16x32_bf16 v[60:63], v[166:169], v[178:181], v[60:63]
	global_load_lds_dwordx4 v0, s[46:47]
	s_waitcnt lgkmcnt(3)
	v_mfma_f32_16x16x32_bf16 v[48:51], v[214:217], v[162:165], v[48:51]
	v_mfma_f32_16x16x32_bf16 v[64:67], v[214:217], v[178:181], v[64:67]
	s_waitcnt lgkmcnt(2)
	v_mfma_f32_16x16x32_bf16 v[174:177], v[218:221], v[162:165], v[174:177]
	ds_read_b128 v[162:165], v16
	v_mfma_f32_16x16x32_bf16 v[170:173], v[218:221], v[178:181], v[170:173]
	ds_read_b128 v[178:181], v17
	s_waitcnt lgkmcnt(3)
	s_mov_b32 m0, s30
	v_mfma_f32_16x16x32_bf16 v[72:75], v[158:161], v[222:225], v[72:75]
	global_load_lds_dwordx4 v0, s[48:49]
	v_mfma_f32_16x16x32_bf16 v[76:79], v[166:169], v[222:225], v[76:79]
	v_mfma_f32_16x16x32_bf16 v[80:83], v[214:217], v[222:225], v[80:83]
	v_mfma_f32_16x16x32_bf16 v[32:35], v[218:221], v[222:225], v[32:35]
	ds_read_b128 v[222:225], v18
	s_waitcnt lgkmcnt(3)
	v_mfma_f32_16x16x32_bf16 v[88:91], v[158:161], v[226:229], v[88:91]
	s_mov_b32 m0, s31
	v_mfma_f32_16x16x32_bf16 v[92:95], v[166:169], v[226:229], v[92:95]
	global_load_lds_dwordx4 v2, s[46:47]
	v_mfma_f32_16x16x32_bf16 v[96:99], v[214:217], v[226:229], v[96:99]
	v_mfma_f32_16x16x32_bf16 v[36:39], v[218:221], v[226:229], v[36:39]
	ds_read_b128 v[226:229], v19
	s_waitcnt lgkmcnt(3)
	v_mfma_f32_16x16x32_bf16 v[104:107], v[158:161], v[162:165], v[104:107]
	s_waitcnt lgkmcnt(2)
	v_mfma_f32_16x16x32_bf16 v[116:119], v[158:161], v[178:181], v[116:119]
	s_waitcnt lgkmcnt(1)
	s_mov_b32 m0, s34
	v_mfma_f32_16x16x32_bf16 v[128:131], v[158:161], v[222:225], v[128:131]
	global_load_lds_dwordx4 v2, s[48:49]
	s_waitcnt lgkmcnt(0)
	v_mfma_f32_16x16x32_bf16 v[100:103], v[158:161], v[226:229], v[100:103]
	ds_read_b128 v[158:161], v20
	v_mfma_f32_16x16x32_bf16 v[108:111], v[166:169], v[162:165], v[108:111]
	v_mfma_f32_16x16x32_bf16 v[120:123], v[166:169], v[178:181], v[120:123]
	v_mfma_f32_16x16x32_bf16 v[132:135], v[166:169], v[222:225], v[132:135]
	s_mov_b32 m0, s35
	v_mfma_f32_16x16x32_bf16 v[140:143], v[166:169], v[226:229], v[140:143]
	global_load_lds_dwordx4 v4, s[46:47]
	ds_read_b128 v[166:169], v24
	v_mfma_f32_16x16x32_bf16 v[112:115], v[214:217], v[162:165], v[112:115]
	v_mfma_f32_16x16x32_bf16 v[52:55], v[218:221], v[162:165], v[52:55]
	ds_read_b128 v[162:165], v21
	v_mfma_f32_16x16x32_bf16 v[124:127], v[214:217], v[178:181], v[124:127]
	v_mfma_f32_16x16x32_bf16 v[68:71], v[218:221], v[178:181], v[68:71]
	ds_read_b128 v[178:181], v25
	s_mov_b32 m0, s36
	v_mfma_f32_16x16x32_bf16 v[136:139], v[214:217], v[222:225], v[136:139]
	global_load_lds_dwordx4 v4, s[48:49]
	v_mfma_f32_16x16x32_bf16 v[84:87], v[218:221], v[222:225], v[84:87]
	ds_read_b128 v[222:225], v26
	v_mfma_f32_16x16x32_bf16 v[150:153], v[214:217], v[226:229], v[150:153]
	ds_read_b128 v[214:217], v23
	v_mfma_f32_16x16x32_bf16 v[154:157], v[218:221], v[226:229], v[154:157]
	ds_read_b128 v[218:221], v22
	ds_read_b128 v[226:229], v27
	s_waitcnt lgkmcnt(6)
	v_mfma_f32_16x16x32_bf16 v[40:43], v[158:161], v[166:169], v[40:43]
	s_waitcnt lgkmcnt(5)
	s_mov_b32 m0, s37
	v_mfma_f32_16x16x32_bf16 v[44:47], v[162:165], v[166:169], v[44:47]
	global_load_lds_dwordx4 v146, s[46:47]
	s_waitcnt lgkmcnt(4)
	v_mfma_f32_16x16x32_bf16 v[56:59], v[158:161], v[178:181], v[56:59]
	v_mfma_f32_16x16x32_bf16 v[60:63], v[162:165], v[178:181], v[60:63]
	s_waitcnt lgkmcnt(3)
	v_mfma_f32_16x16x32_bf16 v[72:75], v[158:161], v[222:225], v[72:75]
	v_mfma_f32_16x16x32_bf16 v[76:79], v[162:165], v[222:225], v[76:79]
	s_waitcnt lgkmcnt(2)
	s_mov_b32 m0, s38
	v_mfma_f32_16x16x32_bf16 v[48:51], v[214:217], v[166:169], v[48:51]
	global_load_lds_dwordx4 v146, s[48:49]
	s_waitcnt lgkmcnt(1)
	v_mfma_f32_16x16x32_bf16 v[174:177], v[218:221], v[166:169], v[174:177]
	ds_read_b128 v[166:169], v28
	v_mfma_f32_16x16x32_bf16 v[64:67], v[214:217], v[178:181], v[64:67]
	v_mfma_f32_16x16x32_bf16 v[170:173], v[218:221], v[178:181], v[170:173]
	ds_read_b128 v[178:181], v29
	v_mfma_f32_16x16x32_bf16 v[80:83], v[214:217], v[222:225], v[80:83]
	v_mfma_f32_16x16x32_bf16 v[32:35], v[218:221], v[222:225], v[32:35]
	ds_read_b128 v[222:225], v30
	s_waitcnt lgkmcnt(3)
	v_mfma_f32_16x16x32_bf16 v[88:91], v[158:161], v[226:229], v[88:91]
	v_mfma_f32_16x16x32_bf16 v[92:95], v[162:165], v[226:229], v[92:95]
	v_mfma_f32_16x16x32_bf16 v[96:99], v[214:217], v[226:229], v[96:99]
	v_mfma_f32_16x16x32_bf16 v[36:39], v[218:221], v[226:229], v[36:39]
	ds_read_b128 v[226:229], v31
	s_waitcnt lgkmcnt(3)
	v_mfma_f32_16x16x32_bf16 v[104:107], v[158:161], v[166:169], v[104:107]
	v_mfma_f32_16x16x32_bf16 v[108:111], v[162:165], v[166:169], v[108:111]
	v_mfma_f32_16x16x32_bf16 v[112:115], v[214:217], v[166:169], v[112:115]
	v_mfma_f32_16x16x32_bf16 v[52:55], v[218:221], v[166:169], v[52:55]
	s_waitcnt lgkmcnt(2)
	v_mfma_f32_16x16x32_bf16 v[116:119], v[158:161], v[178:181], v[116:119]
	v_mfma_f32_16x16x32_bf16 v[120:123], v[162:165], v[178:181], v[120:123]
	v_mfma_f32_16x16x32_bf16 v[124:127], v[214:217], v[178:181], v[124:127]
	v_mfma_f32_16x16x32_bf16 v[68:71], v[218:221], v[178:181], v[68:71]
	s_waitcnt lgkmcnt(1)
	v_mfma_f32_16x16x32_bf16 v[128:131], v[158:161], v[222:225], v[128:131]
	v_mfma_f32_16x16x32_bf16 v[132:135], v[162:165], v[222:225], v[132:135]
	v_mfma_f32_16x16x32_bf16 v[136:139], v[214:217], v[222:225], v[136:139]
	v_mfma_f32_16x16x32_bf16 v[84:87], v[218:221], v[222:225], v[84:87]
	s_waitcnt lgkmcnt(0)
	v_mfma_f32_16x16x32_bf16 v[100:103], v[158:161], v[226:229], v[100:103]
	v_mfma_f32_16x16x32_bf16 v[140:143], v[162:165], v[226:229], v[140:143]
	v_mfma_f32_16x16x32_bf16 v[150:153], v[214:217], v[226:229], v[150:153]
	v_mfma_f32_16x16x32_bf16 v[154:157], v[218:221], v[226:229], v[154:157]
	s_add_u32 s46, s16, 0x580
	s_addc_u32 s47, s17, 0
	s_add_u32 s48, s18, 0x580
	s_waitcnt vmcnt(0)
	s_barrier
	s_addc_u32 s49, s19, 0
	ds_read_b128 v[158:161], v7 offset:32768
	ds_read_b128 v[162:165], v6
	ds_read_b128 v[166:169], v7 offset:34816
	ds_read_b128 v[178:181], v6 offset:2048
	ds_read_b128 v[214:217], v7 offset:36864
	ds_read_b128 v[218:221], v7 offset:38912
	ds_read_b128 v[222:225], v6 offset:4096
	ds_read_b128 v[226:229], v6 offset:6144
	s_waitcnt lgkmcnt(6)
	v_mfma_f32_16x16x32_bf16 v[40:43], v[158:161], v[162:165], v[40:43]
	s_waitcnt lgkmcnt(5)
	v_mfma_f32_16x16x32_bf16 v[44:47], v[166:169], v[162:165], v[44:47]
	s_waitcnt lgkmcnt(4)
	v_mfma_f32_16x16x32_bf16 v[56:59], v[158:161], v[178:181], v[56:59]
	s_mov_b32 m0, s25
	v_mfma_f32_16x16x32_bf16 v[60:63], v[166:169], v[178:181], v[60:63]
	global_load_lds_dwordx4 v0, s[46:47]
	s_waitcnt lgkmcnt(3)
	v_mfma_f32_16x16x32_bf16 v[48:51], v[214:217], v[162:165], v[48:51]
	v_mfma_f32_16x16x32_bf16 v[64:67], v[214:217], v[178:181], v[64:67]
	s_waitcnt lgkmcnt(2)
	v_mfma_f32_16x16x32_bf16 v[174:177], v[218:221], v[162:165], v[174:177]
	ds_read_b128 v[162:165], v6 offset:8192
	v_mfma_f32_16x16x32_bf16 v[170:173], v[218:221], v[178:181], v[170:173]
	ds_read_b128 v[178:181], v6 offset:10240
	s_waitcnt lgkmcnt(3)
	s_mov_b32 m0, s24
	v_mfma_f32_16x16x32_bf16 v[72:75], v[158:161], v[222:225], v[72:75]
	global_load_lds_dwordx4 v0, s[48:49]
	v_mfma_f32_16x16x32_bf16 v[76:79], v[166:169], v[222:225], v[76:79]
	v_mfma_f32_16x16x32_bf16 v[80:83], v[214:217], v[222:225], v[80:83]
	v_mfma_f32_16x16x32_bf16 v[32:35], v[218:221], v[222:225], v[32:35]
	ds_read_b128 v[222:225], v6 offset:12288
	s_waitcnt lgkmcnt(3)
	v_mfma_f32_16x16x32_bf16 v[88:91], v[158:161], v[226:229], v[88:91]
	s_mov_b32 m0, s39
	v_mfma_f32_16x16x32_bf16 v[92:95], v[166:169], v[226:229], v[92:95]
	global_load_lds_dwordx4 v2, s[46:47]
	v_mfma_f32_16x16x32_bf16 v[96:99], v[214:217], v[226:229], v[96:99]
	v_mfma_f32_16x16x32_bf16 v[36:39], v[218:221], v[226:229], v[36:39]
	ds_read_b128 v[226:229], v6 offset:14336
	s_waitcnt lgkmcnt(3)
	v_mfma_f32_16x16x32_bf16 v[104:107], v[158:161], v[162:165], v[104:107]
	s_waitcnt lgkmcnt(2)
	v_mfma_f32_16x16x32_bf16 v[116:119], v[158:161], v[178:181], v[116:119]
	s_waitcnt lgkmcnt(1)
	s_mov_b32 m0, s40
	v_mfma_f32_16x16x32_bf16 v[128:131], v[158:161], v[222:225], v[128:131]
	global_load_lds_dwordx4 v2, s[48:49]
	s_waitcnt lgkmcnt(0)
	v_mfma_f32_16x16x32_bf16 v[100:103], v[158:161], v[226:229], v[100:103]
	ds_read_b128 v[158:161], v7 offset:33792
	v_mfma_f32_16x16x32_bf16 v[108:111], v[166:169], v[162:165], v[108:111]
	v_mfma_f32_16x16x32_bf16 v[120:123], v[166:169], v[178:181], v[120:123]
	v_mfma_f32_16x16x32_bf16 v[132:135], v[166:169], v[222:225], v[132:135]
	s_mov_b32 m0, s41
	v_mfma_f32_16x16x32_bf16 v[140:143], v[166:169], v[226:229], v[140:143]
	global_load_lds_dwordx4 v4, s[46:47]
	ds_read_b128 v[166:169], v6 offset:1024
	v_mfma_f32_16x16x32_bf16 v[112:115], v[214:217], v[162:165], v[112:115]
	v_mfma_f32_16x16x32_bf16 v[52:55], v[218:221], v[162:165], v[52:55]
	ds_read_b128 v[162:165], v7 offset:35840
	v_mfma_f32_16x16x32_bf16 v[124:127], v[214:217], v[178:181], v[124:127]
	v_mfma_f32_16x16x32_bf16 v[68:71], v[218:221], v[178:181], v[68:71]
	ds_read_b128 v[178:181], v6 offset:3072
	s_mov_b32 m0, s42
	v_mfma_f32_16x16x32_bf16 v[136:139], v[214:217], v[222:225], v[136:139]
	global_load_lds_dwordx4 v4, s[48:49]
	v_mfma_f32_16x16x32_bf16 v[84:87], v[218:221], v[222:225], v[84:87]
	ds_read_b128 v[222:225], v6 offset:5120
	v_mfma_f32_16x16x32_bf16 v[150:153], v[214:217], v[226:229], v[150:153]
	ds_read_b128 v[214:217], v7 offset:37888
	v_mfma_f32_16x16x32_bf16 v[154:157], v[218:221], v[226:229], v[154:157]
	ds_read_b128 v[218:221], v7 offset:39936
	ds_read_b128 v[226:229], v6 offset:7168
	s_waitcnt lgkmcnt(6)
	v_mfma_f32_16x16x32_bf16 v[40:43], v[158:161], v[166:169], v[40:43]
	s_waitcnt lgkmcnt(5)
	s_mov_b32 m0, s43
	v_mfma_f32_16x16x32_bf16 v[44:47], v[162:165], v[166:169], v[44:47]
	global_load_lds_dwordx4 v146, s[46:47]
	s_waitcnt lgkmcnt(4)
	v_mfma_f32_16x16x32_bf16 v[56:59], v[158:161], v[178:181], v[56:59]
	v_mfma_f32_16x16x32_bf16 v[60:63], v[162:165], v[178:181], v[60:63]
	s_waitcnt lgkmcnt(3)
	v_mfma_f32_16x16x32_bf16 v[72:75], v[158:161], v[222:225], v[72:75]
	v_mfma_f32_16x16x32_bf16 v[76:79], v[162:165], v[222:225], v[76:79]
	s_waitcnt lgkmcnt(2)
	s_mov_b32 m0, s44
	v_mfma_f32_16x16x32_bf16 v[48:51], v[214:217], v[166:169], v[48:51]
	global_load_lds_dwordx4 v146, s[48:49]
	s_waitcnt lgkmcnt(1)
	v_mfma_f32_16x16x32_bf16 v[174:177], v[218:221], v[166:169], v[174:177]
	ds_read_b128 v[166:169], v6 offset:9216
	v_mfma_f32_16x16x32_bf16 v[64:67], v[214:217], v[178:181], v[64:67]
	v_mfma_f32_16x16x32_bf16 v[170:173], v[218:221], v[178:181], v[170:173]
	ds_read_b128 v[178:181], v6 offset:11264
	v_mfma_f32_16x16x32_bf16 v[80:83], v[214:217], v[222:225], v[80:83]
	v_mfma_f32_16x16x32_bf16 v[32:35], v[218:221], v[222:225], v[32:35]
	ds_read_b128 v[222:225], v6 offset:13312
	s_waitcnt lgkmcnt(3)
	v_mfma_f32_16x16x32_bf16 v[88:91], v[158:161], v[226:229], v[88:91]
	v_mfma_f32_16x16x32_bf16 v[92:95], v[162:165], v[226:229], v[92:95]
	v_mfma_f32_16x16x32_bf16 v[96:99], v[214:217], v[226:229], v[96:99]
	v_mfma_f32_16x16x32_bf16 v[36:39], v[218:221], v[226:229], v[36:39]
	ds_read_b128 v[226:229], v6 offset:15360
	s_waitcnt lgkmcnt(3)
	v_mfma_f32_16x16x32_bf16 v[104:107], v[158:161], v[166:169], v[104:107]
	v_mfma_f32_16x16x32_bf16 v[108:111], v[162:165], v[166:169], v[108:111]
	v_mfma_f32_16x16x32_bf16 v[112:115], v[214:217], v[166:169], v[112:115]
	v_mfma_f32_16x16x32_bf16 v[52:55], v[218:221], v[166:169], v[52:55]
	s_waitcnt lgkmcnt(2)
	v_mfma_f32_16x16x32_bf16 v[116:119], v[158:161], v[178:181], v[116:119]
	v_mfma_f32_16x16x32_bf16 v[120:123], v[162:165], v[178:181], v[120:123]
	v_mfma_f32_16x16x32_bf16 v[124:127], v[214:217], v[178:181], v[124:127]
	v_mfma_f32_16x16x32_bf16 v[68:71], v[218:221], v[178:181], v[68:71]
	s_waitcnt lgkmcnt(1)
	v_mfma_f32_16x16x32_bf16 v[128:131], v[158:161], v[222:225], v[128:131]
	v_mfma_f32_16x16x32_bf16 v[132:135], v[162:165], v[222:225], v[132:135]
	v_mfma_f32_16x16x32_bf16 v[136:139], v[214:217], v[222:225], v[136:139]
	v_mfma_f32_16x16x32_bf16 v[84:87], v[218:221], v[222:225], v[84:87]
	s_waitcnt lgkmcnt(0)
	v_mfma_f32_16x16x32_bf16 v[100:103], v[158:161], v[226:229], v[100:103]
	v_mfma_f32_16x16x32_bf16 v[140:143], v[162:165], v[226:229], v[140:143]
	v_mfma_f32_16x16x32_bf16 v[150:153], v[214:217], v[226:229], v[150:153]
	v_mfma_f32_16x16x32_bf16 v[154:157], v[218:221], v[226:229], v[154:157]
	s_add_u32 s46, s16, 0x600
	s_addc_u32 s47, s17, 0
	s_add_u32 s48, s18, 0x600
	s_waitcnt vmcnt(0)
	s_barrier
	s_addc_u32 s49, s19, 0
	ds_read_b128 v[158:161], v8
	ds_read_b128 v[162:165], v12
	ds_read_b128 v[166:169], v9
	ds_read_b128 v[178:181], v13
	ds_read_b128 v[214:217], v11
	ds_read_b128 v[218:221], v10
	ds_read_b128 v[222:225], v14
	ds_read_b128 v[226:229], v15
	s_waitcnt lgkmcnt(6)
	v_mfma_f32_16x16x32_bf16 v[40:43], v[158:161], v[162:165], v[40:43]
	s_waitcnt lgkmcnt(5)
	v_mfma_f32_16x16x32_bf16 v[44:47], v[166:169], v[162:165], v[44:47]
	s_waitcnt lgkmcnt(4)
	v_mfma_f32_16x16x32_bf16 v[56:59], v[158:161], v[178:181], v[56:59]
	s_mov_b32 m0, s1
	v_mfma_f32_16x16x32_bf16 v[60:63], v[166:169], v[178:181], v[60:63]
	global_load_lds_dwordx4 v0, s[46:47]
	s_waitcnt lgkmcnt(3)
	v_mfma_f32_16x16x32_bf16 v[48:51], v[214:217], v[162:165], v[48:51]
	v_mfma_f32_16x16x32_bf16 v[64:67], v[214:217], v[178:181], v[64:67]
	s_waitcnt lgkmcnt(2)
	v_mfma_f32_16x16x32_bf16 v[174:177], v[218:221], v[162:165], v[174:177]
	ds_read_b128 v[162:165], v16
	v_mfma_f32_16x16x32_bf16 v[170:173], v[218:221], v[178:181], v[170:173]
	ds_read_b128 v[178:181], v17
	s_waitcnt lgkmcnt(3)
	s_mov_b32 m0, s30
	v_mfma_f32_16x16x32_bf16 v[72:75], v[158:161], v[222:225], v[72:75]
	global_load_lds_dwordx4 v0, s[48:49]
	v_mfma_f32_16x16x32_bf16 v[76:79], v[166:169], v[222:225], v[76:79]
	v_mfma_f32_16x16x32_bf16 v[80:83], v[214:217], v[222:225], v[80:83]
	v_mfma_f32_16x16x32_bf16 v[32:35], v[218:221], v[222:225], v[32:35]
	ds_read_b128 v[222:225], v18
	s_waitcnt lgkmcnt(3)
	v_mfma_f32_16x16x32_bf16 v[88:91], v[158:161], v[226:229], v[88:91]
	s_mov_b32 m0, s31
	v_mfma_f32_16x16x32_bf16 v[92:95], v[166:169], v[226:229], v[92:95]
	global_load_lds_dwordx4 v2, s[46:47]
	v_mfma_f32_16x16x32_bf16 v[96:99], v[214:217], v[226:229], v[96:99]
	v_mfma_f32_16x16x32_bf16 v[36:39], v[218:221], v[226:229], v[36:39]
	ds_read_b128 v[226:229], v19
	s_waitcnt lgkmcnt(3)
	v_mfma_f32_16x16x32_bf16 v[104:107], v[158:161], v[162:165], v[104:107]
	s_waitcnt lgkmcnt(2)
	v_mfma_f32_16x16x32_bf16 v[116:119], v[158:161], v[178:181], v[116:119]
	s_waitcnt lgkmcnt(1)
	s_mov_b32 m0, s34
	v_mfma_f32_16x16x32_bf16 v[128:131], v[158:161], v[222:225], v[128:131]
	global_load_lds_dwordx4 v2, s[48:49]
	s_waitcnt lgkmcnt(0)
	v_mfma_f32_16x16x32_bf16 v[100:103], v[158:161], v[226:229], v[100:103]
	ds_read_b128 v[158:161], v20
	v_mfma_f32_16x16x32_bf16 v[108:111], v[166:169], v[162:165], v[108:111]
	v_mfma_f32_16x16x32_bf16 v[120:123], v[166:169], v[178:181], v[120:123]
	v_mfma_f32_16x16x32_bf16 v[132:135], v[166:169], v[222:225], v[132:135]
	s_mov_b32 m0, s35
	v_mfma_f32_16x16x32_bf16 v[140:143], v[166:169], v[226:229], v[140:143]
	global_load_lds_dwordx4 v4, s[46:47]
	ds_read_b128 v[166:169], v24
	v_mfma_f32_16x16x32_bf16 v[112:115], v[214:217], v[162:165], v[112:115]
	v_mfma_f32_16x16x32_bf16 v[52:55], v[218:221], v[162:165], v[52:55]
	ds_read_b128 v[162:165], v21
	v_mfma_f32_16x16x32_bf16 v[124:127], v[214:217], v[178:181], v[124:127]
	v_mfma_f32_16x16x32_bf16 v[68:71], v[218:221], v[178:181], v[68:71]
	ds_read_b128 v[178:181], v25
	s_mov_b32 m0, s36
	v_mfma_f32_16x16x32_bf16 v[136:139], v[214:217], v[222:225], v[136:139]
	global_load_lds_dwordx4 v4, s[48:49]
	v_mfma_f32_16x16x32_bf16 v[84:87], v[218:221], v[222:225], v[84:87]
	ds_read_b128 v[222:225], v26
	v_mfma_f32_16x16x32_bf16 v[150:153], v[214:217], v[226:229], v[150:153]
	ds_read_b128 v[214:217], v23
	v_mfma_f32_16x16x32_bf16 v[154:157], v[218:221], v[226:229], v[154:157]
	ds_read_b128 v[218:221], v22
	ds_read_b128 v[226:229], v27
	s_waitcnt lgkmcnt(6)
	v_mfma_f32_16x16x32_bf16 v[40:43], v[158:161], v[166:169], v[40:43]
	s_waitcnt lgkmcnt(5)
	s_mov_b32 m0, s37
	v_mfma_f32_16x16x32_bf16 v[44:47], v[162:165], v[166:169], v[44:47]
	global_load_lds_dwordx4 v146, s[46:47]
	s_waitcnt lgkmcnt(4)
	v_mfma_f32_16x16x32_bf16 v[56:59], v[158:161], v[178:181], v[56:59]
	v_mfma_f32_16x16x32_bf16 v[60:63], v[162:165], v[178:181], v[60:63]
	s_waitcnt lgkmcnt(3)
	v_mfma_f32_16x16x32_bf16 v[72:75], v[158:161], v[222:225], v[72:75]
	v_mfma_f32_16x16x32_bf16 v[76:79], v[162:165], v[222:225], v[76:79]
	s_waitcnt lgkmcnt(2)
	s_mov_b32 m0, s38
	v_mfma_f32_16x16x32_bf16 v[48:51], v[214:217], v[166:169], v[48:51]
	global_load_lds_dwordx4 v146, s[48:49]
	s_waitcnt lgkmcnt(1)
	v_mfma_f32_16x16x32_bf16 v[174:177], v[218:221], v[166:169], v[174:177]
	ds_read_b128 v[166:169], v28
	v_mfma_f32_16x16x32_bf16 v[64:67], v[214:217], v[178:181], v[64:67]
	v_mfma_f32_16x16x32_bf16 v[170:173], v[218:221], v[178:181], v[170:173]
	ds_read_b128 v[178:181], v29
	v_mfma_f32_16x16x32_bf16 v[80:83], v[214:217], v[222:225], v[80:83]
	v_mfma_f32_16x16x32_bf16 v[32:35], v[218:221], v[222:225], v[32:35]
	ds_read_b128 v[222:225], v30
	s_waitcnt lgkmcnt(3)
	v_mfma_f32_16x16x32_bf16 v[88:91], v[158:161], v[226:229], v[88:91]
	v_mfma_f32_16x16x32_bf16 v[92:95], v[162:165], v[226:229], v[92:95]
	v_mfma_f32_16x16x32_bf16 v[96:99], v[214:217], v[226:229], v[96:99]
	v_mfma_f32_16x16x32_bf16 v[36:39], v[218:221], v[226:229], v[36:39]
	ds_read_b128 v[226:229], v31
	s_waitcnt lgkmcnt(3)
	v_mfma_f32_16x16x32_bf16 v[104:107], v[158:161], v[166:169], v[104:107]
	v_mfma_f32_16x16x32_bf16 v[108:111], v[162:165], v[166:169], v[108:111]
	v_mfma_f32_16x16x32_bf16 v[112:115], v[214:217], v[166:169], v[112:115]
	v_mfma_f32_16x16x32_bf16 v[52:55], v[218:221], v[166:169], v[52:55]
	s_waitcnt lgkmcnt(2)
	v_mfma_f32_16x16x32_bf16 v[116:119], v[158:161], v[178:181], v[116:119]
	v_mfma_f32_16x16x32_bf16 v[120:123], v[162:165], v[178:181], v[120:123]
	v_mfma_f32_16x16x32_bf16 v[124:127], v[214:217], v[178:181], v[124:127]
	v_mfma_f32_16x16x32_bf16 v[68:71], v[218:221], v[178:181], v[68:71]
	s_waitcnt lgkmcnt(1)
	v_mfma_f32_16x16x32_bf16 v[128:131], v[158:161], v[222:225], v[128:131]
	v_mfma_f32_16x16x32_bf16 v[132:135], v[162:165], v[222:225], v[132:135]
	v_mfma_f32_16x16x32_bf16 v[136:139], v[214:217], v[222:225], v[136:139]
	v_mfma_f32_16x16x32_bf16 v[84:87], v[218:221], v[222:225], v[84:87]
	s_waitcnt lgkmcnt(0)
	v_mfma_f32_16x16x32_bf16 v[100:103], v[158:161], v[226:229], v[100:103]
	v_mfma_f32_16x16x32_bf16 v[140:143], v[162:165], v[226:229], v[140:143]
	v_mfma_f32_16x16x32_bf16 v[150:153], v[214:217], v[226:229], v[150:153]
	v_mfma_f32_16x16x32_bf16 v[154:157], v[218:221], v[226:229], v[154:157]
	s_add_u32 s46, s16, 0x680
	s_addc_u32 s47, s17, 0
	s_add_u32 s48, s18, 0x680
	s_waitcnt vmcnt(0)
	s_barrier
	s_addc_u32 s49, s19, 0
	ds_read_b128 v[158:161], v7 offset:32768
	ds_read_b128 v[162:165], v6
	ds_read_b128 v[166:169], v7 offset:34816
	ds_read_b128 v[178:181], v6 offset:2048
	ds_read_b128 v[214:217], v7 offset:36864
	ds_read_b128 v[218:221], v7 offset:38912
	ds_read_b128 v[222:225], v6 offset:4096
	ds_read_b128 v[226:229], v6 offset:6144
	s_waitcnt lgkmcnt(6)
	v_mfma_f32_16x16x32_bf16 v[40:43], v[158:161], v[162:165], v[40:43]
	s_waitcnt lgkmcnt(5)
	v_mfma_f32_16x16x32_bf16 v[44:47], v[166:169], v[162:165], v[44:47]
	s_waitcnt lgkmcnt(4)
	v_mfma_f32_16x16x32_bf16 v[56:59], v[158:161], v[178:181], v[56:59]
	s_mov_b32 m0, s25
	v_mfma_f32_16x16x32_bf16 v[60:63], v[166:169], v[178:181], v[60:63]
	global_load_lds_dwordx4 v0, s[46:47]
	s_waitcnt lgkmcnt(3)
	v_mfma_f32_16x16x32_bf16 v[48:51], v[214:217], v[162:165], v[48:51]
	v_mfma_f32_16x16x32_bf16 v[64:67], v[214:217], v[178:181], v[64:67]
	s_waitcnt lgkmcnt(2)
	v_mfma_f32_16x16x32_bf16 v[174:177], v[218:221], v[162:165], v[174:177]
	ds_read_b128 v[162:165], v6 offset:8192
	v_mfma_f32_16x16x32_bf16 v[170:173], v[218:221], v[178:181], v[170:173]
	ds_read_b128 v[178:181], v6 offset:10240
	s_waitcnt lgkmcnt(3)
	s_mov_b32 m0, s24
	v_mfma_f32_16x16x32_bf16 v[72:75], v[158:161], v[222:225], v[72:75]
	global_load_lds_dwordx4 v0, s[48:49]
	v_mfma_f32_16x16x32_bf16 v[76:79], v[166:169], v[222:225], v[76:79]
	v_mfma_f32_16x16x32_bf16 v[80:83], v[214:217], v[222:225], v[80:83]
	v_mfma_f32_16x16x32_bf16 v[32:35], v[218:221], v[222:225], v[32:35]
	ds_read_b128 v[222:225], v6 offset:12288
	s_waitcnt lgkmcnt(3)
	v_mfma_f32_16x16x32_bf16 v[88:91], v[158:161], v[226:229], v[88:91]
	s_mov_b32 m0, s39
	v_mfma_f32_16x16x32_bf16 v[92:95], v[166:169], v[226:229], v[92:95]
	global_load_lds_dwordx4 v2, s[46:47]
	v_mfma_f32_16x16x32_bf16 v[96:99], v[214:217], v[226:229], v[96:99]
	v_mfma_f32_16x16x32_bf16 v[36:39], v[218:221], v[226:229], v[36:39]
	ds_read_b128 v[226:229], v6 offset:14336
	s_waitcnt lgkmcnt(3)
	v_mfma_f32_16x16x32_bf16 v[104:107], v[158:161], v[162:165], v[104:107]
	s_waitcnt lgkmcnt(2)
	v_mfma_f32_16x16x32_bf16 v[116:119], v[158:161], v[178:181], v[116:119]
	s_waitcnt lgkmcnt(1)
	s_mov_b32 m0, s40
	v_mfma_f32_16x16x32_bf16 v[128:131], v[158:161], v[222:225], v[128:131]
	global_load_lds_dwordx4 v2, s[48:49]
	s_waitcnt lgkmcnt(0)
	v_mfma_f32_16x16x32_bf16 v[100:103], v[158:161], v[226:229], v[100:103]
	ds_read_b128 v[158:161], v7 offset:33792
	v_mfma_f32_16x16x32_bf16 v[108:111], v[166:169], v[162:165], v[108:111]
	v_mfma_f32_16x16x32_bf16 v[120:123], v[166:169], v[178:181], v[120:123]
	v_mfma_f32_16x16x32_bf16 v[132:135], v[166:169], v[222:225], v[132:135]
	s_mov_b32 m0, s41
	v_mfma_f32_16x16x32_bf16 v[140:143], v[166:169], v[226:229], v[140:143]
	global_load_lds_dwordx4 v4, s[46:47]
	ds_read_b128 v[166:169], v6 offset:1024
	v_mfma_f32_16x16x32_bf16 v[112:115], v[214:217], v[162:165], v[112:115]
	v_mfma_f32_16x16x32_bf16 v[52:55], v[218:221], v[162:165], v[52:55]
	ds_read_b128 v[162:165], v7 offset:35840
	v_mfma_f32_16x16x32_bf16 v[124:127], v[214:217], v[178:181], v[124:127]
	v_mfma_f32_16x16x32_bf16 v[68:71], v[218:221], v[178:181], v[68:71]
	ds_read_b128 v[178:181], v6 offset:3072
	s_mov_b32 m0, s42
	v_mfma_f32_16x16x32_bf16 v[136:139], v[214:217], v[222:225], v[136:139]
	global_load_lds_dwordx4 v4, s[48:49]
	v_mfma_f32_16x16x32_bf16 v[84:87], v[218:221], v[222:225], v[84:87]
	ds_read_b128 v[222:225], v6 offset:5120
	v_mfma_f32_16x16x32_bf16 v[150:153], v[214:217], v[226:229], v[150:153]
	ds_read_b128 v[214:217], v7 offset:37888
	v_mfma_f32_16x16x32_bf16 v[154:157], v[218:221], v[226:229], v[154:157]
	ds_read_b128 v[218:221], v7 offset:39936
	ds_read_b128 v[226:229], v6 offset:7168
	s_waitcnt lgkmcnt(6)
	v_mfma_f32_16x16x32_bf16 v[40:43], v[158:161], v[166:169], v[40:43]
	s_waitcnt lgkmcnt(5)
	s_mov_b32 m0, s43
	v_mfma_f32_16x16x32_bf16 v[44:47], v[162:165], v[166:169], v[44:47]
	global_load_lds_dwordx4 v146, s[46:47]
	s_waitcnt lgkmcnt(4)
	v_mfma_f32_16x16x32_bf16 v[56:59], v[158:161], v[178:181], v[56:59]
	v_mfma_f32_16x16x32_bf16 v[60:63], v[162:165], v[178:181], v[60:63]
	s_waitcnt lgkmcnt(3)
	v_mfma_f32_16x16x32_bf16 v[72:75], v[158:161], v[222:225], v[72:75]
	v_mfma_f32_16x16x32_bf16 v[76:79], v[162:165], v[222:225], v[76:79]
	s_waitcnt lgkmcnt(2)
	s_mov_b32 m0, s44
	v_mfma_f32_16x16x32_bf16 v[48:51], v[214:217], v[166:169], v[48:51]
	global_load_lds_dwordx4 v146, s[48:49]
	s_waitcnt lgkmcnt(1)
	v_mfma_f32_16x16x32_bf16 v[174:177], v[218:221], v[166:169], v[174:177]
	ds_read_b128 v[166:169], v6 offset:9216
	v_mfma_f32_16x16x32_bf16 v[64:67], v[214:217], v[178:181], v[64:67]
	v_mfma_f32_16x16x32_bf16 v[170:173], v[218:221], v[178:181], v[170:173]
	ds_read_b128 v[178:181], v6 offset:11264
	v_mfma_f32_16x16x32_bf16 v[80:83], v[214:217], v[222:225], v[80:83]
	v_mfma_f32_16x16x32_bf16 v[32:35], v[218:221], v[222:225], v[32:35]
	ds_read_b128 v[222:225], v6 offset:13312
	s_waitcnt lgkmcnt(3)
	v_mfma_f32_16x16x32_bf16 v[88:91], v[158:161], v[226:229], v[88:91]
	v_mfma_f32_16x16x32_bf16 v[92:95], v[162:165], v[226:229], v[92:95]
	v_mfma_f32_16x16x32_bf16 v[96:99], v[214:217], v[226:229], v[96:99]
	v_mfma_f32_16x16x32_bf16 v[36:39], v[218:221], v[226:229], v[36:39]
	ds_read_b128 v[226:229], v6 offset:15360
	s_waitcnt lgkmcnt(3)
	v_mfma_f32_16x16x32_bf16 v[104:107], v[158:161], v[166:169], v[104:107]
	v_mfma_f32_16x16x32_bf16 v[108:111], v[162:165], v[166:169], v[108:111]
	v_mfma_f32_16x16x32_bf16 v[112:115], v[214:217], v[166:169], v[112:115]
	v_mfma_f32_16x16x32_bf16 v[52:55], v[218:221], v[166:169], v[52:55]
	s_waitcnt lgkmcnt(2)
	v_mfma_f32_16x16x32_bf16 v[116:119], v[158:161], v[178:181], v[116:119]
	v_mfma_f32_16x16x32_bf16 v[120:123], v[162:165], v[178:181], v[120:123]
	v_mfma_f32_16x16x32_bf16 v[124:127], v[214:217], v[178:181], v[124:127]
	v_mfma_f32_16x16x32_bf16 v[68:71], v[218:221], v[178:181], v[68:71]
	s_waitcnt lgkmcnt(1)
	v_mfma_f32_16x16x32_bf16 v[128:131], v[158:161], v[222:225], v[128:131]
	v_mfma_f32_16x16x32_bf16 v[132:135], v[162:165], v[222:225], v[132:135]
	v_mfma_f32_16x16x32_bf16 v[136:139], v[214:217], v[222:225], v[136:139]
	v_mfma_f32_16x16x32_bf16 v[84:87], v[218:221], v[222:225], v[84:87]
	s_waitcnt lgkmcnt(0)
	v_mfma_f32_16x16x32_bf16 v[100:103], v[158:161], v[226:229], v[100:103]
	v_mfma_f32_16x16x32_bf16 v[140:143], v[162:165], v[226:229], v[140:143]
	v_mfma_f32_16x16x32_bf16 v[150:153], v[214:217], v[226:229], v[150:153]
	v_mfma_f32_16x16x32_bf16 v[154:157], v[218:221], v[226:229], v[154:157]
	s_add_u32 s46, s16, 0x700
	s_addc_u32 s47, s17, 0
	s_add_u32 s48, s18, 0x700
	s_waitcnt vmcnt(0)
	s_barrier
	s_addc_u32 s49, s19, 0
	ds_read_b128 v[158:161], v8
	ds_read_b128 v[162:165], v12
	ds_read_b128 v[166:169], v9
	ds_read_b128 v[178:181], v13
	ds_read_b128 v[214:217], v11
	ds_read_b128 v[218:221], v10
	ds_read_b128 v[222:225], v14
	ds_read_b128 v[226:229], v15
	s_waitcnt lgkmcnt(6)
	v_mfma_f32_16x16x32_bf16 v[40:43], v[158:161], v[162:165], v[40:43]
	s_waitcnt lgkmcnt(5)
	v_mfma_f32_16x16x32_bf16 v[44:47], v[166:169], v[162:165], v[44:47]
	s_waitcnt lgkmcnt(4)
	v_mfma_f32_16x16x32_bf16 v[56:59], v[158:161], v[178:181], v[56:59]
	s_mov_b32 m0, s1
	v_mfma_f32_16x16x32_bf16 v[60:63], v[166:169], v[178:181], v[60:63]
	global_load_lds_dwordx4 v0, s[46:47]
	s_waitcnt lgkmcnt(3)
	v_mfma_f32_16x16x32_bf16 v[48:51], v[214:217], v[162:165], v[48:51]
	v_mfma_f32_16x16x32_bf16 v[64:67], v[214:217], v[178:181], v[64:67]
	s_waitcnt lgkmcnt(2)
	v_mfma_f32_16x16x32_bf16 v[174:177], v[218:221], v[162:165], v[174:177]
	ds_read_b128 v[162:165], v16
	v_mfma_f32_16x16x32_bf16 v[170:173], v[218:221], v[178:181], v[170:173]
	ds_read_b128 v[178:181], v17
	s_waitcnt lgkmcnt(3)
	s_mov_b32 m0, s30
	v_mfma_f32_16x16x32_bf16 v[72:75], v[158:161], v[222:225], v[72:75]
	global_load_lds_dwordx4 v0, s[48:49]
	v_mfma_f32_16x16x32_bf16 v[76:79], v[166:169], v[222:225], v[76:79]
	v_mfma_f32_16x16x32_bf16 v[80:83], v[214:217], v[222:225], v[80:83]
	v_mfma_f32_16x16x32_bf16 v[32:35], v[218:221], v[222:225], v[32:35]
	ds_read_b128 v[222:225], v18
	s_waitcnt lgkmcnt(3)
	v_mfma_f32_16x16x32_bf16 v[88:91], v[158:161], v[226:229], v[88:91]
	s_mov_b32 m0, s31
	v_mfma_f32_16x16x32_bf16 v[92:95], v[166:169], v[226:229], v[92:95]
	global_load_lds_dwordx4 v2, s[46:47]
	v_mfma_f32_16x16x32_bf16 v[96:99], v[214:217], v[226:229], v[96:99]
	v_mfma_f32_16x16x32_bf16 v[36:39], v[218:221], v[226:229], v[36:39]
	ds_read_b128 v[226:229], v19
	s_waitcnt lgkmcnt(3)
	v_mfma_f32_16x16x32_bf16 v[104:107], v[158:161], v[162:165], v[104:107]
	s_waitcnt lgkmcnt(2)
	v_mfma_f32_16x16x32_bf16 v[116:119], v[158:161], v[178:181], v[116:119]
	s_waitcnt lgkmcnt(1)
	s_mov_b32 m0, s34
	v_mfma_f32_16x16x32_bf16 v[128:131], v[158:161], v[222:225], v[128:131]
	global_load_lds_dwordx4 v2, s[48:49]
	s_waitcnt lgkmcnt(0)
	v_mfma_f32_16x16x32_bf16 v[100:103], v[158:161], v[226:229], v[100:103]
	ds_read_b128 v[158:161], v20
	v_mfma_f32_16x16x32_bf16 v[108:111], v[166:169], v[162:165], v[108:111]
	v_mfma_f32_16x16x32_bf16 v[120:123], v[166:169], v[178:181], v[120:123]
	v_mfma_f32_16x16x32_bf16 v[132:135], v[166:169], v[222:225], v[132:135]
	s_mov_b32 m0, s35
	v_mfma_f32_16x16x32_bf16 v[140:143], v[166:169], v[226:229], v[140:143]
	global_load_lds_dwordx4 v4, s[46:47]
	ds_read_b128 v[166:169], v24
	v_mfma_f32_16x16x32_bf16 v[112:115], v[214:217], v[162:165], v[112:115]
	v_mfma_f32_16x16x32_bf16 v[52:55], v[218:221], v[162:165], v[52:55]
	ds_read_b128 v[162:165], v21
	v_mfma_f32_16x16x32_bf16 v[124:127], v[214:217], v[178:181], v[124:127]
	v_mfma_f32_16x16x32_bf16 v[68:71], v[218:221], v[178:181], v[68:71]
	ds_read_b128 v[178:181], v25
	s_mov_b32 m0, s36
	v_mfma_f32_16x16x32_bf16 v[136:139], v[214:217], v[222:225], v[136:139]
	global_load_lds_dwordx4 v4, s[48:49]
	v_mfma_f32_16x16x32_bf16 v[84:87], v[218:221], v[222:225], v[84:87]
	ds_read_b128 v[222:225], v26
	v_mfma_f32_16x16x32_bf16 v[150:153], v[214:217], v[226:229], v[150:153]
	ds_read_b128 v[214:217], v23
	v_mfma_f32_16x16x32_bf16 v[154:157], v[218:221], v[226:229], v[154:157]
	ds_read_b128 v[218:221], v22
	ds_read_b128 v[226:229], v27
	s_waitcnt lgkmcnt(6)
	v_mfma_f32_16x16x32_bf16 v[40:43], v[158:161], v[166:169], v[40:43]
	s_waitcnt lgkmcnt(5)
	s_mov_b32 m0, s37
	v_mfma_f32_16x16x32_bf16 v[44:47], v[162:165], v[166:169], v[44:47]
	global_load_lds_dwordx4 v146, s[46:47]
	s_waitcnt lgkmcnt(4)
	v_mfma_f32_16x16x32_bf16 v[56:59], v[158:161], v[178:181], v[56:59]
	v_mfma_f32_16x16x32_bf16 v[60:63], v[162:165], v[178:181], v[60:63]
	s_waitcnt lgkmcnt(3)
	v_mfma_f32_16x16x32_bf16 v[72:75], v[158:161], v[222:225], v[72:75]
	v_mfma_f32_16x16x32_bf16 v[76:79], v[162:165], v[222:225], v[76:79]
	s_waitcnt lgkmcnt(2)
	s_mov_b32 m0, s38
	v_mfma_f32_16x16x32_bf16 v[48:51], v[214:217], v[166:169], v[48:51]
	global_load_lds_dwordx4 v146, s[48:49]
	s_waitcnt lgkmcnt(1)
	v_mfma_f32_16x16x32_bf16 v[174:177], v[218:221], v[166:169], v[174:177]
	ds_read_b128 v[166:169], v28
	v_mfma_f32_16x16x32_bf16 v[64:67], v[214:217], v[178:181], v[64:67]
	v_mfma_f32_16x16x32_bf16 v[170:173], v[218:221], v[178:181], v[170:173]
	ds_read_b128 v[178:181], v29
	v_mfma_f32_16x16x32_bf16 v[80:83], v[214:217], v[222:225], v[80:83]
	v_mfma_f32_16x16x32_bf16 v[32:35], v[218:221], v[222:225], v[32:35]
	ds_read_b128 v[222:225], v30
	s_waitcnt lgkmcnt(3)
	v_mfma_f32_16x16x32_bf16 v[88:91], v[158:161], v[226:229], v[88:91]
	v_mfma_f32_16x16x32_bf16 v[92:95], v[162:165], v[226:229], v[92:95]
	v_mfma_f32_16x16x32_bf16 v[96:99], v[214:217], v[226:229], v[96:99]
	v_mfma_f32_16x16x32_bf16 v[36:39], v[218:221], v[226:229], v[36:39]
	ds_read_b128 v[226:229], v31
	s_waitcnt lgkmcnt(3)
	v_mfma_f32_16x16x32_bf16 v[104:107], v[158:161], v[166:169], v[104:107]
	v_mfma_f32_16x16x32_bf16 v[108:111], v[162:165], v[166:169], v[108:111]
	v_mfma_f32_16x16x32_bf16 v[112:115], v[214:217], v[166:169], v[112:115]
	v_mfma_f32_16x16x32_bf16 v[52:55], v[218:221], v[166:169], v[52:55]
	s_waitcnt lgkmcnt(2)
	v_mfma_f32_16x16x32_bf16 v[116:119], v[158:161], v[178:181], v[116:119]
	v_mfma_f32_16x16x32_bf16 v[120:123], v[162:165], v[178:181], v[120:123]
	v_mfma_f32_16x16x32_bf16 v[124:127], v[214:217], v[178:181], v[124:127]
	v_mfma_f32_16x16x32_bf16 v[68:71], v[218:221], v[178:181], v[68:71]
	s_waitcnt lgkmcnt(1)
	v_mfma_f32_16x16x32_bf16 v[128:131], v[158:161], v[222:225], v[128:131]
	v_mfma_f32_16x16x32_bf16 v[132:135], v[162:165], v[222:225], v[132:135]
	v_mfma_f32_16x16x32_bf16 v[136:139], v[214:217], v[222:225], v[136:139]
	v_mfma_f32_16x16x32_bf16 v[84:87], v[218:221], v[222:225], v[84:87]
	s_waitcnt lgkmcnt(0)
	v_mfma_f32_16x16x32_bf16 v[100:103], v[158:161], v[226:229], v[100:103]
	v_mfma_f32_16x16x32_bf16 v[140:143], v[162:165], v[226:229], v[140:143]
	v_mfma_f32_16x16x32_bf16 v[150:153], v[214:217], v[226:229], v[150:153]
	v_mfma_f32_16x16x32_bf16 v[154:157], v[218:221], v[226:229], v[154:157]
	s_add_u32 s46, s16, 0x780
	s_addc_u32 s47, s17, 0
	s_add_u32 s48, s18, 0x780
	s_waitcnt vmcnt(0)
	s_barrier
	s_addc_u32 s49, s19, 0
	ds_read_b128 v[158:161], v7 offset:32768
	ds_read_b128 v[162:165], v6
	ds_read_b128 v[166:169], v7 offset:34816
	ds_read_b128 v[178:181], v6 offset:2048
	ds_read_b128 v[214:217], v7 offset:36864
	ds_read_b128 v[218:221], v7 offset:38912
	ds_read_b128 v[222:225], v6 offset:4096
	ds_read_b128 v[226:229], v6 offset:6144
	s_waitcnt lgkmcnt(6)
	v_mfma_f32_16x16x32_bf16 v[40:43], v[158:161], v[162:165], v[40:43]
	s_waitcnt lgkmcnt(5)
	v_mfma_f32_16x16x32_bf16 v[44:47], v[166:169], v[162:165], v[44:47]
	s_waitcnt lgkmcnt(4)
	v_mfma_f32_16x16x32_bf16 v[56:59], v[158:161], v[178:181], v[56:59]
	s_mov_b32 m0, s25
	v_mfma_f32_16x16x32_bf16 v[60:63], v[166:169], v[178:181], v[60:63]
	global_load_lds_dwordx4 v0, s[46:47]
	s_waitcnt lgkmcnt(3)
	v_mfma_f32_16x16x32_bf16 v[48:51], v[214:217], v[162:165], v[48:51]
	v_mfma_f32_16x16x32_bf16 v[64:67], v[214:217], v[178:181], v[64:67]
	s_waitcnt lgkmcnt(2)
	v_mfma_f32_16x16x32_bf16 v[174:177], v[218:221], v[162:165], v[174:177]
	ds_read_b128 v[162:165], v6 offset:8192
	v_mfma_f32_16x16x32_bf16 v[170:173], v[218:221], v[178:181], v[170:173]
	ds_read_b128 v[178:181], v6 offset:10240
	s_waitcnt lgkmcnt(3)
	s_mov_b32 m0, s24
	v_mfma_f32_16x16x32_bf16 v[72:75], v[158:161], v[222:225], v[72:75]
	global_load_lds_dwordx4 v0, s[48:49]
	v_mfma_f32_16x16x32_bf16 v[76:79], v[166:169], v[222:225], v[76:79]
	v_mfma_f32_16x16x32_bf16 v[80:83], v[214:217], v[222:225], v[80:83]
	v_mfma_f32_16x16x32_bf16 v[32:35], v[218:221], v[222:225], v[32:35]
	ds_read_b128 v[222:225], v6 offset:12288
	s_waitcnt lgkmcnt(3)
	v_mfma_f32_16x16x32_bf16 v[88:91], v[158:161], v[226:229], v[88:91]
	s_mov_b32 m0, s39
	v_mfma_f32_16x16x32_bf16 v[92:95], v[166:169], v[226:229], v[92:95]
	global_load_lds_dwordx4 v2, s[46:47]
	v_mfma_f32_16x16x32_bf16 v[96:99], v[214:217], v[226:229], v[96:99]
	v_mfma_f32_16x16x32_bf16 v[36:39], v[218:221], v[226:229], v[36:39]
	ds_read_b128 v[226:229], v6 offset:14336
	s_waitcnt lgkmcnt(3)
	v_mfma_f32_16x16x32_bf16 v[104:107], v[158:161], v[162:165], v[104:107]
	s_waitcnt lgkmcnt(2)
	v_mfma_f32_16x16x32_bf16 v[116:119], v[158:161], v[178:181], v[116:119]
	s_waitcnt lgkmcnt(1)
	s_mov_b32 m0, s40
	v_mfma_f32_16x16x32_bf16 v[128:131], v[158:161], v[222:225], v[128:131]
	global_load_lds_dwordx4 v2, s[48:49]
	s_waitcnt lgkmcnt(0)
	v_mfma_f32_16x16x32_bf16 v[100:103], v[158:161], v[226:229], v[100:103]
	ds_read_b128 v[158:161], v7 offset:33792
	v_mfma_f32_16x16x32_bf16 v[108:111], v[166:169], v[162:165], v[108:111]
	v_mfma_f32_16x16x32_bf16 v[120:123], v[166:169], v[178:181], v[120:123]
	v_mfma_f32_16x16x32_bf16 v[132:135], v[166:169], v[222:225], v[132:135]
	s_mov_b32 m0, s41
	v_mfma_f32_16x16x32_bf16 v[140:143], v[166:169], v[226:229], v[140:143]
	global_load_lds_dwordx4 v4, s[46:47]
	ds_read_b128 v[166:169], v6 offset:1024
	v_mfma_f32_16x16x32_bf16 v[112:115], v[214:217], v[162:165], v[112:115]
	v_mfma_f32_16x16x32_bf16 v[52:55], v[218:221], v[162:165], v[52:55]
	ds_read_b128 v[162:165], v7 offset:35840
	v_mfma_f32_16x16x32_bf16 v[124:127], v[214:217], v[178:181], v[124:127]
	v_mfma_f32_16x16x32_bf16 v[68:71], v[218:221], v[178:181], v[68:71]
	ds_read_b128 v[178:181], v6 offset:3072
	s_mov_b32 m0, s42
	v_mfma_f32_16x16x32_bf16 v[136:139], v[214:217], v[222:225], v[136:139]
	global_load_lds_dwordx4 v4, s[48:49]
	v_mfma_f32_16x16x32_bf16 v[84:87], v[218:221], v[222:225], v[84:87]
	ds_read_b128 v[222:225], v6 offset:5120
	v_mfma_f32_16x16x32_bf16 v[150:153], v[214:217], v[226:229], v[150:153]
	ds_read_b128 v[214:217], v7 offset:37888
	v_mfma_f32_16x16x32_bf16 v[154:157], v[218:221], v[226:229], v[154:157]
	ds_read_b128 v[218:221], v7 offset:39936
	ds_read_b128 v[226:229], v6 offset:7168
	s_waitcnt lgkmcnt(6)
	v_mfma_f32_16x16x32_bf16 v[40:43], v[158:161], v[166:169], v[40:43]
	s_waitcnt lgkmcnt(5)
	s_mov_b32 m0, s43
	v_mfma_f32_16x16x32_bf16 v[44:47], v[162:165], v[166:169], v[44:47]
	global_load_lds_dwordx4 v146, s[46:47]
	s_waitcnt lgkmcnt(4)
	v_mfma_f32_16x16x32_bf16 v[56:59], v[158:161], v[178:181], v[56:59]
	v_mfma_f32_16x16x32_bf16 v[60:63], v[162:165], v[178:181], v[60:63]
	s_waitcnt lgkmcnt(3)
	v_mfma_f32_16x16x32_bf16 v[72:75], v[158:161], v[222:225], v[72:75]
	v_mfma_f32_16x16x32_bf16 v[76:79], v[162:165], v[222:225], v[76:79]
	s_waitcnt lgkmcnt(2)
	s_mov_b32 m0, s44
	v_mfma_f32_16x16x32_bf16 v[48:51], v[214:217], v[166:169], v[48:51]
	global_load_lds_dwordx4 v146, s[48:49]
	s_waitcnt lgkmcnt(1)
	v_mfma_f32_16x16x32_bf16 v[174:177], v[218:221], v[166:169], v[174:177]
	ds_read_b128 v[166:169], v6 offset:9216
	v_mfma_f32_16x16x32_bf16 v[64:67], v[214:217], v[178:181], v[64:67]
	v_mfma_f32_16x16x32_bf16 v[170:173], v[218:221], v[178:181], v[170:173]
	ds_read_b128 v[178:181], v6 offset:11264
	v_mfma_f32_16x16x32_bf16 v[80:83], v[214:217], v[222:225], v[80:83]
	v_mfma_f32_16x16x32_bf16 v[32:35], v[218:221], v[222:225], v[32:35]
	ds_read_b128 v[222:225], v6 offset:13312
	s_waitcnt lgkmcnt(3)
	v_mfma_f32_16x16x32_bf16 v[88:91], v[158:161], v[226:229], v[88:91]
	v_mfma_f32_16x16x32_bf16 v[92:95], v[162:165], v[226:229], v[92:95]
	v_mfma_f32_16x16x32_bf16 v[96:99], v[214:217], v[226:229], v[96:99]
	v_mfma_f32_16x16x32_bf16 v[36:39], v[218:221], v[226:229], v[36:39]
	ds_read_b128 v[226:229], v6 offset:15360
	s_waitcnt lgkmcnt(3)
	v_mfma_f32_16x16x32_bf16 v[104:107], v[158:161], v[166:169], v[104:107]
	v_mfma_f32_16x16x32_bf16 v[108:111], v[162:165], v[166:169], v[108:111]
	v_mfma_f32_16x16x32_bf16 v[112:115], v[214:217], v[166:169], v[112:115]
	v_mfma_f32_16x16x32_bf16 v[52:55], v[218:221], v[166:169], v[52:55]
	s_waitcnt lgkmcnt(2)
	v_mfma_f32_16x16x32_bf16 v[116:119], v[158:161], v[178:181], v[116:119]
	v_mfma_f32_16x16x32_bf16 v[120:123], v[162:165], v[178:181], v[120:123]
	v_mfma_f32_16x16x32_bf16 v[124:127], v[214:217], v[178:181], v[124:127]
	v_mfma_f32_16x16x32_bf16 v[68:71], v[218:221], v[178:181], v[68:71]
	s_waitcnt lgkmcnt(1)
	v_mfma_f32_16x16x32_bf16 v[128:131], v[158:161], v[222:225], v[128:131]
	v_mfma_f32_16x16x32_bf16 v[132:135], v[162:165], v[222:225], v[132:135]
	v_mfma_f32_16x16x32_bf16 v[136:139], v[214:217], v[222:225], v[136:139]
	v_mfma_f32_16x16x32_bf16 v[84:87], v[218:221], v[222:225], v[84:87]
	s_waitcnt lgkmcnt(0)
	v_mfma_f32_16x16x32_bf16 v[100:103], v[158:161], v[226:229], v[100:103]
	v_mfma_f32_16x16x32_bf16 v[140:143], v[162:165], v[226:229], v[140:143]
	v_mfma_f32_16x16x32_bf16 v[150:153], v[214:217], v[226:229], v[150:153]
	v_mfma_f32_16x16x32_bf16 v[154:157], v[218:221], v[226:229], v[154:157]
	s_add_u32 s46, s16, 0x800
	s_addc_u32 s47, s17, 0
	s_add_u32 s48, s18, 0x800
	s_waitcnt vmcnt(0)
	s_barrier
	s_addc_u32 s49, s19, 0
	ds_read_b128 v[158:161], v8
	ds_read_b128 v[162:165], v12
	ds_read_b128 v[166:169], v9
	ds_read_b128 v[178:181], v13
	ds_read_b128 v[214:217], v11
	ds_read_b128 v[218:221], v10
	ds_read_b128 v[222:225], v14
	ds_read_b128 v[226:229], v15
	s_waitcnt lgkmcnt(6)
	v_mfma_f32_16x16x32_bf16 v[40:43], v[158:161], v[162:165], v[40:43]
	s_waitcnt lgkmcnt(5)
	v_mfma_f32_16x16x32_bf16 v[44:47], v[166:169], v[162:165], v[44:47]
	s_waitcnt lgkmcnt(4)
	v_mfma_f32_16x16x32_bf16 v[56:59], v[158:161], v[178:181], v[56:59]
	s_mov_b32 m0, s1
	v_mfma_f32_16x16x32_bf16 v[60:63], v[166:169], v[178:181], v[60:63]
	global_load_lds_dwordx4 v0, s[46:47]
	s_waitcnt lgkmcnt(3)
	v_mfma_f32_16x16x32_bf16 v[48:51], v[214:217], v[162:165], v[48:51]
	v_mfma_f32_16x16x32_bf16 v[64:67], v[214:217], v[178:181], v[64:67]
	s_waitcnt lgkmcnt(2)
	v_mfma_f32_16x16x32_bf16 v[174:177], v[218:221], v[162:165], v[174:177]
	ds_read_b128 v[162:165], v16
	v_mfma_f32_16x16x32_bf16 v[170:173], v[218:221], v[178:181], v[170:173]
	ds_read_b128 v[178:181], v17
	s_waitcnt lgkmcnt(3)
	s_mov_b32 m0, s30
	v_mfma_f32_16x16x32_bf16 v[72:75], v[158:161], v[222:225], v[72:75]
	global_load_lds_dwordx4 v0, s[48:49]
	v_mfma_f32_16x16x32_bf16 v[76:79], v[166:169], v[222:225], v[76:79]
	v_mfma_f32_16x16x32_bf16 v[80:83], v[214:217], v[222:225], v[80:83]
	v_mfma_f32_16x16x32_bf16 v[32:35], v[218:221], v[222:225], v[32:35]
	ds_read_b128 v[222:225], v18
	s_waitcnt lgkmcnt(3)
	v_mfma_f32_16x16x32_bf16 v[88:91], v[158:161], v[226:229], v[88:91]
	s_mov_b32 m0, s31
	v_mfma_f32_16x16x32_bf16 v[92:95], v[166:169], v[226:229], v[92:95]
	global_load_lds_dwordx4 v2, s[46:47]
	v_mfma_f32_16x16x32_bf16 v[96:99], v[214:217], v[226:229], v[96:99]
	v_mfma_f32_16x16x32_bf16 v[36:39], v[218:221], v[226:229], v[36:39]
	ds_read_b128 v[226:229], v19
	s_waitcnt lgkmcnt(3)
	v_mfma_f32_16x16x32_bf16 v[104:107], v[158:161], v[162:165], v[104:107]
	s_waitcnt lgkmcnt(2)
	v_mfma_f32_16x16x32_bf16 v[116:119], v[158:161], v[178:181], v[116:119]
	s_waitcnt lgkmcnt(1)
	s_mov_b32 m0, s34
	v_mfma_f32_16x16x32_bf16 v[128:131], v[158:161], v[222:225], v[128:131]
	global_load_lds_dwordx4 v2, s[48:49]
	s_waitcnt lgkmcnt(0)
	v_mfma_f32_16x16x32_bf16 v[100:103], v[158:161], v[226:229], v[100:103]
	ds_read_b128 v[158:161], v20
	v_mfma_f32_16x16x32_bf16 v[108:111], v[166:169], v[162:165], v[108:111]
	v_mfma_f32_16x16x32_bf16 v[120:123], v[166:169], v[178:181], v[120:123]
	v_mfma_f32_16x16x32_bf16 v[132:135], v[166:169], v[222:225], v[132:135]
	s_mov_b32 m0, s35
	v_mfma_f32_16x16x32_bf16 v[140:143], v[166:169], v[226:229], v[140:143]
	global_load_lds_dwordx4 v4, s[46:47]
	ds_read_b128 v[166:169], v24
	v_mfma_f32_16x16x32_bf16 v[112:115], v[214:217], v[162:165], v[112:115]
	v_mfma_f32_16x16x32_bf16 v[52:55], v[218:221], v[162:165], v[52:55]
	ds_read_b128 v[162:165], v21
	v_mfma_f32_16x16x32_bf16 v[124:127], v[214:217], v[178:181], v[124:127]
	v_mfma_f32_16x16x32_bf16 v[68:71], v[218:221], v[178:181], v[68:71]
	ds_read_b128 v[178:181], v25
	s_mov_b32 m0, s36
	v_mfma_f32_16x16x32_bf16 v[136:139], v[214:217], v[222:225], v[136:139]
	global_load_lds_dwordx4 v4, s[48:49]
	v_mfma_f32_16x16x32_bf16 v[84:87], v[218:221], v[222:225], v[84:87]
	ds_read_b128 v[222:225], v26
	v_mfma_f32_16x16x32_bf16 v[150:153], v[214:217], v[226:229], v[150:153]
	ds_read_b128 v[214:217], v23
	v_mfma_f32_16x16x32_bf16 v[154:157], v[218:221], v[226:229], v[154:157]
	ds_read_b128 v[218:221], v22
	ds_read_b128 v[226:229], v27
	s_waitcnt lgkmcnt(6)
	v_mfma_f32_16x16x32_bf16 v[40:43], v[158:161], v[166:169], v[40:43]
	s_waitcnt lgkmcnt(5)
	s_mov_b32 m0, s37
	v_mfma_f32_16x16x32_bf16 v[44:47], v[162:165], v[166:169], v[44:47]
	global_load_lds_dwordx4 v146, s[46:47]
	s_waitcnt lgkmcnt(4)
	v_mfma_f32_16x16x32_bf16 v[56:59], v[158:161], v[178:181], v[56:59]
	v_mfma_f32_16x16x32_bf16 v[60:63], v[162:165], v[178:181], v[60:63]
	s_waitcnt lgkmcnt(3)
	v_mfma_f32_16x16x32_bf16 v[72:75], v[158:161], v[222:225], v[72:75]
	v_mfma_f32_16x16x32_bf16 v[76:79], v[162:165], v[222:225], v[76:79]
	s_waitcnt lgkmcnt(2)
	s_mov_b32 m0, s38
	v_mfma_f32_16x16x32_bf16 v[48:51], v[214:217], v[166:169], v[48:51]
	global_load_lds_dwordx4 v146, s[48:49]
	s_waitcnt lgkmcnt(1)
	v_mfma_f32_16x16x32_bf16 v[174:177], v[218:221], v[166:169], v[174:177]
	ds_read_b128 v[166:169], v28
	v_mfma_f32_16x16x32_bf16 v[64:67], v[214:217], v[178:181], v[64:67]
	v_mfma_f32_16x16x32_bf16 v[170:173], v[218:221], v[178:181], v[170:173]
	ds_read_b128 v[178:181], v29
	v_mfma_f32_16x16x32_bf16 v[80:83], v[214:217], v[222:225], v[80:83]
	v_mfma_f32_16x16x32_bf16 v[32:35], v[218:221], v[222:225], v[32:35]
	ds_read_b128 v[222:225], v30
	s_waitcnt lgkmcnt(3)
	v_mfma_f32_16x16x32_bf16 v[88:91], v[158:161], v[226:229], v[88:91]
	v_mfma_f32_16x16x32_bf16 v[92:95], v[162:165], v[226:229], v[92:95]
	v_mfma_f32_16x16x32_bf16 v[96:99], v[214:217], v[226:229], v[96:99]
	v_mfma_f32_16x16x32_bf16 v[36:39], v[218:221], v[226:229], v[36:39]
	ds_read_b128 v[226:229], v31
	s_waitcnt lgkmcnt(3)
	v_mfma_f32_16x16x32_bf16 v[104:107], v[158:161], v[166:169], v[104:107]
	v_mfma_f32_16x16x32_bf16 v[108:111], v[162:165], v[166:169], v[108:111]
	v_mfma_f32_16x16x32_bf16 v[112:115], v[214:217], v[166:169], v[112:115]
	v_mfma_f32_16x16x32_bf16 v[52:55], v[218:221], v[166:169], v[52:55]
	s_waitcnt lgkmcnt(2)
	v_mfma_f32_16x16x32_bf16 v[116:119], v[158:161], v[178:181], v[116:119]
	v_mfma_f32_16x16x32_bf16 v[120:123], v[162:165], v[178:181], v[120:123]
	v_mfma_f32_16x16x32_bf16 v[124:127], v[214:217], v[178:181], v[124:127]
	v_mfma_f32_16x16x32_bf16 v[68:71], v[218:221], v[178:181], v[68:71]
	s_waitcnt lgkmcnt(1)
	v_mfma_f32_16x16x32_bf16 v[128:131], v[158:161], v[222:225], v[128:131]
	v_mfma_f32_16x16x32_bf16 v[132:135], v[162:165], v[222:225], v[132:135]
	v_mfma_f32_16x16x32_bf16 v[136:139], v[214:217], v[222:225], v[136:139]
	v_mfma_f32_16x16x32_bf16 v[84:87], v[218:221], v[222:225], v[84:87]
	s_waitcnt lgkmcnt(0)
	v_mfma_f32_16x16x32_bf16 v[100:103], v[158:161], v[226:229], v[100:103]
	v_mfma_f32_16x16x32_bf16 v[140:143], v[162:165], v[226:229], v[140:143]
	v_mfma_f32_16x16x32_bf16 v[150:153], v[214:217], v[226:229], v[150:153]
	v_mfma_f32_16x16x32_bf16 v[154:157], v[218:221], v[226:229], v[154:157]
	s_add_u32 s46, s16, 0x880
	s_addc_u32 s47, s17, 0
	s_add_u32 s48, s18, 0x880
	s_waitcnt vmcnt(0)
	s_barrier
	s_addc_u32 s49, s19, 0
	ds_read_b128 v[158:161], v7 offset:32768
	ds_read_b128 v[162:165], v6
	ds_read_b128 v[166:169], v7 offset:34816
	ds_read_b128 v[178:181], v6 offset:2048
	ds_read_b128 v[214:217], v7 offset:36864
	ds_read_b128 v[218:221], v7 offset:38912
	ds_read_b128 v[222:225], v6 offset:4096
	ds_read_b128 v[226:229], v6 offset:6144
	s_waitcnt lgkmcnt(6)
	v_mfma_f32_16x16x32_bf16 v[40:43], v[158:161], v[162:165], v[40:43]
	s_waitcnt lgkmcnt(5)
	v_mfma_f32_16x16x32_bf16 v[44:47], v[166:169], v[162:165], v[44:47]
	s_waitcnt lgkmcnt(4)
	v_mfma_f32_16x16x32_bf16 v[56:59], v[158:161], v[178:181], v[56:59]
	s_mov_b32 m0, s25
	v_mfma_f32_16x16x32_bf16 v[60:63], v[166:169], v[178:181], v[60:63]
	global_load_lds_dwordx4 v0, s[46:47]
	s_waitcnt lgkmcnt(3)
	v_mfma_f32_16x16x32_bf16 v[48:51], v[214:217], v[162:165], v[48:51]
	v_mfma_f32_16x16x32_bf16 v[64:67], v[214:217], v[178:181], v[64:67]
	s_waitcnt lgkmcnt(2)
	v_mfma_f32_16x16x32_bf16 v[174:177], v[218:221], v[162:165], v[174:177]
	ds_read_b128 v[162:165], v6 offset:8192
	v_mfma_f32_16x16x32_bf16 v[170:173], v[218:221], v[178:181], v[170:173]
	ds_read_b128 v[178:181], v6 offset:10240
	s_waitcnt lgkmcnt(3)
	s_mov_b32 m0, s24
	v_mfma_f32_16x16x32_bf16 v[72:75], v[158:161], v[222:225], v[72:75]
	global_load_lds_dwordx4 v0, s[48:49]
	v_mfma_f32_16x16x32_bf16 v[76:79], v[166:169], v[222:225], v[76:79]
	v_mfma_f32_16x16x32_bf16 v[80:83], v[214:217], v[222:225], v[80:83]
	v_mfma_f32_16x16x32_bf16 v[32:35], v[218:221], v[222:225], v[32:35]
	ds_read_b128 v[222:225], v6 offset:12288
	s_waitcnt lgkmcnt(3)
	v_mfma_f32_16x16x32_bf16 v[88:91], v[158:161], v[226:229], v[88:91]
	s_mov_b32 m0, s39
	v_mfma_f32_16x16x32_bf16 v[92:95], v[166:169], v[226:229], v[92:95]
	global_load_lds_dwordx4 v2, s[46:47]
	v_mfma_f32_16x16x32_bf16 v[96:99], v[214:217], v[226:229], v[96:99]
	v_mfma_f32_16x16x32_bf16 v[36:39], v[218:221], v[226:229], v[36:39]
	ds_read_b128 v[226:229], v6 offset:14336
	s_waitcnt lgkmcnt(3)
	v_mfma_f32_16x16x32_bf16 v[104:107], v[158:161], v[162:165], v[104:107]
	s_waitcnt lgkmcnt(2)
	v_mfma_f32_16x16x32_bf16 v[116:119], v[158:161], v[178:181], v[116:119]
	s_waitcnt lgkmcnt(1)
	s_mov_b32 m0, s40
	v_mfma_f32_16x16x32_bf16 v[128:131], v[158:161], v[222:225], v[128:131]
	global_load_lds_dwordx4 v2, s[48:49]
	s_waitcnt lgkmcnt(0)
	v_mfma_f32_16x16x32_bf16 v[100:103], v[158:161], v[226:229], v[100:103]
	ds_read_b128 v[158:161], v7 offset:33792
	v_mfma_f32_16x16x32_bf16 v[108:111], v[166:169], v[162:165], v[108:111]
	v_mfma_f32_16x16x32_bf16 v[120:123], v[166:169], v[178:181], v[120:123]
	v_mfma_f32_16x16x32_bf16 v[132:135], v[166:169], v[222:225], v[132:135]
	s_mov_b32 m0, s41
	v_mfma_f32_16x16x32_bf16 v[140:143], v[166:169], v[226:229], v[140:143]
	global_load_lds_dwordx4 v4, s[46:47]
	ds_read_b128 v[166:169], v6 offset:1024
	v_mfma_f32_16x16x32_bf16 v[112:115], v[214:217], v[162:165], v[112:115]
	v_mfma_f32_16x16x32_bf16 v[52:55], v[218:221], v[162:165], v[52:55]
	ds_read_b128 v[162:165], v7 offset:35840
	v_mfma_f32_16x16x32_bf16 v[124:127], v[214:217], v[178:181], v[124:127]
	v_mfma_f32_16x16x32_bf16 v[68:71], v[218:221], v[178:181], v[68:71]
	ds_read_b128 v[178:181], v6 offset:3072
	s_mov_b32 m0, s42
	v_mfma_f32_16x16x32_bf16 v[136:139], v[214:217], v[222:225], v[136:139]
	global_load_lds_dwordx4 v4, s[48:49]
	v_mfma_f32_16x16x32_bf16 v[84:87], v[218:221], v[222:225], v[84:87]
	ds_read_b128 v[222:225], v6 offset:5120
	v_mfma_f32_16x16x32_bf16 v[150:153], v[214:217], v[226:229], v[150:153]
	ds_read_b128 v[214:217], v7 offset:37888
	v_mfma_f32_16x16x32_bf16 v[154:157], v[218:221], v[226:229], v[154:157]
	ds_read_b128 v[218:221], v7 offset:39936
	ds_read_b128 v[226:229], v6 offset:7168
	s_waitcnt lgkmcnt(6)
	v_mfma_f32_16x16x32_bf16 v[40:43], v[158:161], v[166:169], v[40:43]
	s_waitcnt lgkmcnt(5)
	s_mov_b32 m0, s43
	v_mfma_f32_16x16x32_bf16 v[44:47], v[162:165], v[166:169], v[44:47]
	global_load_lds_dwordx4 v146, s[46:47]
	s_waitcnt lgkmcnt(4)
	v_mfma_f32_16x16x32_bf16 v[56:59], v[158:161], v[178:181], v[56:59]
	v_mfma_f32_16x16x32_bf16 v[60:63], v[162:165], v[178:181], v[60:63]
	s_waitcnt lgkmcnt(3)
	v_mfma_f32_16x16x32_bf16 v[72:75], v[158:161], v[222:225], v[72:75]
	v_mfma_f32_16x16x32_bf16 v[76:79], v[162:165], v[222:225], v[76:79]
	s_waitcnt lgkmcnt(2)
	s_mov_b32 m0, s44
	v_mfma_f32_16x16x32_bf16 v[48:51], v[214:217], v[166:169], v[48:51]
	global_load_lds_dwordx4 v146, s[48:49]
	s_waitcnt lgkmcnt(1)
	v_mfma_f32_16x16x32_bf16 v[174:177], v[218:221], v[166:169], v[174:177]
	ds_read_b128 v[166:169], v6 offset:9216
	v_mfma_f32_16x16x32_bf16 v[64:67], v[214:217], v[178:181], v[64:67]
	v_mfma_f32_16x16x32_bf16 v[170:173], v[218:221], v[178:181], v[170:173]
	ds_read_b128 v[178:181], v6 offset:11264
	v_mfma_f32_16x16x32_bf16 v[80:83], v[214:217], v[222:225], v[80:83]
	v_mfma_f32_16x16x32_bf16 v[32:35], v[218:221], v[222:225], v[32:35]
	ds_read_b128 v[222:225], v6 offset:13312
	s_waitcnt lgkmcnt(3)
	v_mfma_f32_16x16x32_bf16 v[88:91], v[158:161], v[226:229], v[88:91]
	v_mfma_f32_16x16x32_bf16 v[92:95], v[162:165], v[226:229], v[92:95]
	v_mfma_f32_16x16x32_bf16 v[96:99], v[214:217], v[226:229], v[96:99]
	v_mfma_f32_16x16x32_bf16 v[36:39], v[218:221], v[226:229], v[36:39]
	ds_read_b128 v[226:229], v6 offset:15360
	s_waitcnt lgkmcnt(3)
	v_mfma_f32_16x16x32_bf16 v[104:107], v[158:161], v[166:169], v[104:107]
	v_mfma_f32_16x16x32_bf16 v[108:111], v[162:165], v[166:169], v[108:111]
	v_mfma_f32_16x16x32_bf16 v[112:115], v[214:217], v[166:169], v[112:115]
	v_mfma_f32_16x16x32_bf16 v[52:55], v[218:221], v[166:169], v[52:55]
	s_waitcnt lgkmcnt(2)
	v_mfma_f32_16x16x32_bf16 v[116:119], v[158:161], v[178:181], v[116:119]
	v_mfma_f32_16x16x32_bf16 v[120:123], v[162:165], v[178:181], v[120:123]
	v_mfma_f32_16x16x32_bf16 v[124:127], v[214:217], v[178:181], v[124:127]
	v_mfma_f32_16x16x32_bf16 v[68:71], v[218:221], v[178:181], v[68:71]
	s_waitcnt lgkmcnt(1)
	v_mfma_f32_16x16x32_bf16 v[128:131], v[158:161], v[222:225], v[128:131]
	v_mfma_f32_16x16x32_bf16 v[132:135], v[162:165], v[222:225], v[132:135]
	v_mfma_f32_16x16x32_bf16 v[136:139], v[214:217], v[222:225], v[136:139]
	v_mfma_f32_16x16x32_bf16 v[84:87], v[218:221], v[222:225], v[84:87]
	s_waitcnt lgkmcnt(0)
	v_mfma_f32_16x16x32_bf16 v[100:103], v[158:161], v[226:229], v[100:103]
	v_mfma_f32_16x16x32_bf16 v[140:143], v[162:165], v[226:229], v[140:143]
	v_mfma_f32_16x16x32_bf16 v[150:153], v[214:217], v[226:229], v[150:153]
	v_mfma_f32_16x16x32_bf16 v[154:157], v[218:221], v[226:229], v[154:157]
	s_add_u32 s46, s16, 0x900
	s_addc_u32 s47, s17, 0
	s_add_u32 s48, s18, 0x900
	s_waitcnt vmcnt(0)
	s_barrier
	s_addc_u32 s49, s19, 0
	ds_read_b128 v[158:161], v8
	ds_read_b128 v[162:165], v12
	ds_read_b128 v[166:169], v9
	ds_read_b128 v[178:181], v13
	ds_read_b128 v[214:217], v11
	ds_read_b128 v[218:221], v10
	ds_read_b128 v[222:225], v14
	ds_read_b128 v[226:229], v15
	s_waitcnt lgkmcnt(6)
	v_mfma_f32_16x16x32_bf16 v[40:43], v[158:161], v[162:165], v[40:43]
	s_waitcnt lgkmcnt(5)
	v_mfma_f32_16x16x32_bf16 v[44:47], v[166:169], v[162:165], v[44:47]
	s_waitcnt lgkmcnt(4)
	v_mfma_f32_16x16x32_bf16 v[56:59], v[158:161], v[178:181], v[56:59]
	s_mov_b32 m0, s1
	v_mfma_f32_16x16x32_bf16 v[60:63], v[166:169], v[178:181], v[60:63]
	global_load_lds_dwordx4 v0, s[46:47]
	s_waitcnt lgkmcnt(3)
	v_mfma_f32_16x16x32_bf16 v[48:51], v[214:217], v[162:165], v[48:51]
	v_mfma_f32_16x16x32_bf16 v[64:67], v[214:217], v[178:181], v[64:67]
	s_waitcnt lgkmcnt(2)
	v_mfma_f32_16x16x32_bf16 v[174:177], v[218:221], v[162:165], v[174:177]
	ds_read_b128 v[162:165], v16
	v_mfma_f32_16x16x32_bf16 v[170:173], v[218:221], v[178:181], v[170:173]
	ds_read_b128 v[178:181], v17
	s_waitcnt lgkmcnt(3)
	s_mov_b32 m0, s30
	v_mfma_f32_16x16x32_bf16 v[72:75], v[158:161], v[222:225], v[72:75]
	global_load_lds_dwordx4 v0, s[48:49]
	v_mfma_f32_16x16x32_bf16 v[76:79], v[166:169], v[222:225], v[76:79]
	v_mfma_f32_16x16x32_bf16 v[80:83], v[214:217], v[222:225], v[80:83]
	v_mfma_f32_16x16x32_bf16 v[32:35], v[218:221], v[222:225], v[32:35]
	ds_read_b128 v[222:225], v18
	s_waitcnt lgkmcnt(3)
	v_mfma_f32_16x16x32_bf16 v[88:91], v[158:161], v[226:229], v[88:91]
	s_mov_b32 m0, s31
	v_mfma_f32_16x16x32_bf16 v[92:95], v[166:169], v[226:229], v[92:95]
	global_load_lds_dwordx4 v2, s[46:47]
	v_mfma_f32_16x16x32_bf16 v[96:99], v[214:217], v[226:229], v[96:99]
	v_mfma_f32_16x16x32_bf16 v[36:39], v[218:221], v[226:229], v[36:39]
	ds_read_b128 v[226:229], v19
	s_waitcnt lgkmcnt(3)
	v_mfma_f32_16x16x32_bf16 v[104:107], v[158:161], v[162:165], v[104:107]
	s_waitcnt lgkmcnt(2)
	v_mfma_f32_16x16x32_bf16 v[116:119], v[158:161], v[178:181], v[116:119]
	s_waitcnt lgkmcnt(1)
	s_mov_b32 m0, s34
	v_mfma_f32_16x16x32_bf16 v[128:131], v[158:161], v[222:225], v[128:131]
	global_load_lds_dwordx4 v2, s[48:49]
	s_waitcnt lgkmcnt(0)
	v_mfma_f32_16x16x32_bf16 v[100:103], v[158:161], v[226:229], v[100:103]
	ds_read_b128 v[158:161], v20
	v_mfma_f32_16x16x32_bf16 v[108:111], v[166:169], v[162:165], v[108:111]
	v_mfma_f32_16x16x32_bf16 v[120:123], v[166:169], v[178:181], v[120:123]
	v_mfma_f32_16x16x32_bf16 v[132:135], v[166:169], v[222:225], v[132:135]
	s_mov_b32 m0, s35
	v_mfma_f32_16x16x32_bf16 v[140:143], v[166:169], v[226:229], v[140:143]
	global_load_lds_dwordx4 v4, s[46:47]
	ds_read_b128 v[166:169], v24
	v_mfma_f32_16x16x32_bf16 v[112:115], v[214:217], v[162:165], v[112:115]
	v_mfma_f32_16x16x32_bf16 v[52:55], v[218:221], v[162:165], v[52:55]
	ds_read_b128 v[162:165], v21
	v_mfma_f32_16x16x32_bf16 v[124:127], v[214:217], v[178:181], v[124:127]
	v_mfma_f32_16x16x32_bf16 v[68:71], v[218:221], v[178:181], v[68:71]
	ds_read_b128 v[178:181], v25
	s_mov_b32 m0, s36
	v_mfma_f32_16x16x32_bf16 v[136:139], v[214:217], v[222:225], v[136:139]
	global_load_lds_dwordx4 v4, s[48:49]
	v_mfma_f32_16x16x32_bf16 v[84:87], v[218:221], v[222:225], v[84:87]
	ds_read_b128 v[222:225], v26
	v_mfma_f32_16x16x32_bf16 v[150:153], v[214:217], v[226:229], v[150:153]
	ds_read_b128 v[214:217], v23
	v_mfma_f32_16x16x32_bf16 v[154:157], v[218:221], v[226:229], v[154:157]
	ds_read_b128 v[218:221], v22
	ds_read_b128 v[226:229], v27
	s_waitcnt lgkmcnt(6)
	v_mfma_f32_16x16x32_bf16 v[40:43], v[158:161], v[166:169], v[40:43]
	s_waitcnt lgkmcnt(5)
	s_mov_b32 m0, s37
	v_mfma_f32_16x16x32_bf16 v[44:47], v[162:165], v[166:169], v[44:47]
	global_load_lds_dwordx4 v146, s[46:47]
	s_waitcnt lgkmcnt(4)
	v_mfma_f32_16x16x32_bf16 v[56:59], v[158:161], v[178:181], v[56:59]
	v_mfma_f32_16x16x32_bf16 v[60:63], v[162:165], v[178:181], v[60:63]
	s_waitcnt lgkmcnt(3)
	v_mfma_f32_16x16x32_bf16 v[72:75], v[158:161], v[222:225], v[72:75]
	v_mfma_f32_16x16x32_bf16 v[76:79], v[162:165], v[222:225], v[76:79]
	s_waitcnt lgkmcnt(2)
	s_mov_b32 m0, s38
	v_mfma_f32_16x16x32_bf16 v[48:51], v[214:217], v[166:169], v[48:51]
	global_load_lds_dwordx4 v146, s[48:49]
	s_waitcnt lgkmcnt(1)
	v_mfma_f32_16x16x32_bf16 v[174:177], v[218:221], v[166:169], v[174:177]
	ds_read_b128 v[166:169], v28
	v_mfma_f32_16x16x32_bf16 v[64:67], v[214:217], v[178:181], v[64:67]
	v_mfma_f32_16x16x32_bf16 v[170:173], v[218:221], v[178:181], v[170:173]
	ds_read_b128 v[178:181], v29
	v_mfma_f32_16x16x32_bf16 v[80:83], v[214:217], v[222:225], v[80:83]
	v_mfma_f32_16x16x32_bf16 v[32:35], v[218:221], v[222:225], v[32:35]
	ds_read_b128 v[222:225], v30
	s_waitcnt lgkmcnt(3)
	v_mfma_f32_16x16x32_bf16 v[88:91], v[158:161], v[226:229], v[88:91]
	v_mfma_f32_16x16x32_bf16 v[92:95], v[162:165], v[226:229], v[92:95]
	v_mfma_f32_16x16x32_bf16 v[96:99], v[214:217], v[226:229], v[96:99]
	v_mfma_f32_16x16x32_bf16 v[36:39], v[218:221], v[226:229], v[36:39]
	ds_read_b128 v[226:229], v31
	s_waitcnt lgkmcnt(3)
	v_mfma_f32_16x16x32_bf16 v[104:107], v[158:161], v[166:169], v[104:107]
	v_mfma_f32_16x16x32_bf16 v[108:111], v[162:165], v[166:169], v[108:111]
	v_mfma_f32_16x16x32_bf16 v[112:115], v[214:217], v[166:169], v[112:115]
	v_mfma_f32_16x16x32_bf16 v[52:55], v[218:221], v[166:169], v[52:55]
	s_waitcnt lgkmcnt(2)
	v_mfma_f32_16x16x32_bf16 v[116:119], v[158:161], v[178:181], v[116:119]
	v_mfma_f32_16x16x32_bf16 v[120:123], v[162:165], v[178:181], v[120:123]
	v_mfma_f32_16x16x32_bf16 v[124:127], v[214:217], v[178:181], v[124:127]
	v_mfma_f32_16x16x32_bf16 v[68:71], v[218:221], v[178:181], v[68:71]
	s_waitcnt lgkmcnt(1)
	v_mfma_f32_16x16x32_bf16 v[128:131], v[158:161], v[222:225], v[128:131]
	v_mfma_f32_16x16x32_bf16 v[132:135], v[162:165], v[222:225], v[132:135]
	v_mfma_f32_16x16x32_bf16 v[136:139], v[214:217], v[222:225], v[136:139]
	v_mfma_f32_16x16x32_bf16 v[84:87], v[218:221], v[222:225], v[84:87]
	s_waitcnt lgkmcnt(0)
	v_mfma_f32_16x16x32_bf16 v[100:103], v[158:161], v[226:229], v[100:103]
	v_mfma_f32_16x16x32_bf16 v[140:143], v[162:165], v[226:229], v[140:143]
	v_mfma_f32_16x16x32_bf16 v[150:153], v[214:217], v[226:229], v[150:153]
	v_mfma_f32_16x16x32_bf16 v[154:157], v[218:221], v[226:229], v[154:157]
	s_add_u32 s46, s16, 0x980
	s_addc_u32 s47, s17, 0
	s_add_u32 s48, s18, 0x980
	s_waitcnt vmcnt(0)
	s_barrier
	s_addc_u32 s49, s19, 0
	ds_read_b128 v[158:161], v7 offset:32768
	ds_read_b128 v[162:165], v6
	ds_read_b128 v[166:169], v7 offset:34816
	ds_read_b128 v[178:181], v6 offset:2048
	ds_read_b128 v[214:217], v7 offset:36864
	ds_read_b128 v[218:221], v7 offset:38912
	ds_read_b128 v[222:225], v6 offset:4096
	ds_read_b128 v[226:229], v6 offset:6144
	s_waitcnt lgkmcnt(6)
	v_mfma_f32_16x16x32_bf16 v[40:43], v[158:161], v[162:165], v[40:43]
	s_waitcnt lgkmcnt(5)
	v_mfma_f32_16x16x32_bf16 v[44:47], v[166:169], v[162:165], v[44:47]
	s_waitcnt lgkmcnt(4)
	v_mfma_f32_16x16x32_bf16 v[56:59], v[158:161], v[178:181], v[56:59]
	s_mov_b32 m0, s25
	v_mfma_f32_16x16x32_bf16 v[60:63], v[166:169], v[178:181], v[60:63]
	global_load_lds_dwordx4 v0, s[46:47]
	s_waitcnt lgkmcnt(3)
	v_mfma_f32_16x16x32_bf16 v[48:51], v[214:217], v[162:165], v[48:51]
	v_mfma_f32_16x16x32_bf16 v[64:67], v[214:217], v[178:181], v[64:67]
	s_waitcnt lgkmcnt(2)
	v_mfma_f32_16x16x32_bf16 v[174:177], v[218:221], v[162:165], v[174:177]
	ds_read_b128 v[162:165], v6 offset:8192
	v_mfma_f32_16x16x32_bf16 v[170:173], v[218:221], v[178:181], v[170:173]
	ds_read_b128 v[178:181], v6 offset:10240
	s_waitcnt lgkmcnt(3)
	s_mov_b32 m0, s24
	v_mfma_f32_16x16x32_bf16 v[72:75], v[158:161], v[222:225], v[72:75]
	global_load_lds_dwordx4 v0, s[48:49]
	v_mfma_f32_16x16x32_bf16 v[76:79], v[166:169], v[222:225], v[76:79]
	v_mfma_f32_16x16x32_bf16 v[80:83], v[214:217], v[222:225], v[80:83]
	v_mfma_f32_16x16x32_bf16 v[32:35], v[218:221], v[222:225], v[32:35]
	ds_read_b128 v[222:225], v6 offset:12288
	s_waitcnt lgkmcnt(3)
	v_mfma_f32_16x16x32_bf16 v[88:91], v[158:161], v[226:229], v[88:91]
	s_mov_b32 m0, s39
	v_mfma_f32_16x16x32_bf16 v[92:95], v[166:169], v[226:229], v[92:95]
	global_load_lds_dwordx4 v2, s[46:47]
	v_mfma_f32_16x16x32_bf16 v[96:99], v[214:217], v[226:229], v[96:99]
	v_mfma_f32_16x16x32_bf16 v[36:39], v[218:221], v[226:229], v[36:39]
	ds_read_b128 v[226:229], v6 offset:14336
	s_waitcnt lgkmcnt(3)
	v_mfma_f32_16x16x32_bf16 v[104:107], v[158:161], v[162:165], v[104:107]
	s_waitcnt lgkmcnt(2)
	v_mfma_f32_16x16x32_bf16 v[116:119], v[158:161], v[178:181], v[116:119]
	s_waitcnt lgkmcnt(1)
	s_mov_b32 m0, s40
	v_mfma_f32_16x16x32_bf16 v[128:131], v[158:161], v[222:225], v[128:131]
	global_load_lds_dwordx4 v2, s[48:49]
	s_waitcnt lgkmcnt(0)
	v_mfma_f32_16x16x32_bf16 v[100:103], v[158:161], v[226:229], v[100:103]
	ds_read_b128 v[158:161], v7 offset:33792
	v_mfma_f32_16x16x32_bf16 v[108:111], v[166:169], v[162:165], v[108:111]
	v_mfma_f32_16x16x32_bf16 v[120:123], v[166:169], v[178:181], v[120:123]
	v_mfma_f32_16x16x32_bf16 v[132:135], v[166:169], v[222:225], v[132:135]
	s_mov_b32 m0, s41
	v_mfma_f32_16x16x32_bf16 v[140:143], v[166:169], v[226:229], v[140:143]
	global_load_lds_dwordx4 v4, s[46:47]
	ds_read_b128 v[166:169], v6 offset:1024
	v_mfma_f32_16x16x32_bf16 v[112:115], v[214:217], v[162:165], v[112:115]
	v_mfma_f32_16x16x32_bf16 v[52:55], v[218:221], v[162:165], v[52:55]
	ds_read_b128 v[162:165], v7 offset:35840
	v_mfma_f32_16x16x32_bf16 v[124:127], v[214:217], v[178:181], v[124:127]
	v_mfma_f32_16x16x32_bf16 v[68:71], v[218:221], v[178:181], v[68:71]
	ds_read_b128 v[178:181], v6 offset:3072
	s_mov_b32 m0, s42
	v_mfma_f32_16x16x32_bf16 v[136:139], v[214:217], v[222:225], v[136:139]
	global_load_lds_dwordx4 v4, s[48:49]
	v_mfma_f32_16x16x32_bf16 v[84:87], v[218:221], v[222:225], v[84:87]
	ds_read_b128 v[222:225], v6 offset:5120
	v_mfma_f32_16x16x32_bf16 v[150:153], v[214:217], v[226:229], v[150:153]
	ds_read_b128 v[214:217], v7 offset:37888
	v_mfma_f32_16x16x32_bf16 v[154:157], v[218:221], v[226:229], v[154:157]
	ds_read_b128 v[218:221], v7 offset:39936
	ds_read_b128 v[226:229], v6 offset:7168
	s_waitcnt lgkmcnt(6)
	v_mfma_f32_16x16x32_bf16 v[40:43], v[158:161], v[166:169], v[40:43]
	s_waitcnt lgkmcnt(5)
	s_mov_b32 m0, s43
	v_mfma_f32_16x16x32_bf16 v[44:47], v[162:165], v[166:169], v[44:47]
	global_load_lds_dwordx4 v146, s[46:47]
	s_waitcnt lgkmcnt(4)
	v_mfma_f32_16x16x32_bf16 v[56:59], v[158:161], v[178:181], v[56:59]
	v_mfma_f32_16x16x32_bf16 v[60:63], v[162:165], v[178:181], v[60:63]
	s_waitcnt lgkmcnt(3)
	v_mfma_f32_16x16x32_bf16 v[72:75], v[158:161], v[222:225], v[72:75]
	v_mfma_f32_16x16x32_bf16 v[76:79], v[162:165], v[222:225], v[76:79]
	s_waitcnt lgkmcnt(2)
	s_mov_b32 m0, s44
	v_mfma_f32_16x16x32_bf16 v[48:51], v[214:217], v[166:169], v[48:51]
	global_load_lds_dwordx4 v146, s[48:49]
	s_waitcnt lgkmcnt(1)
	v_mfma_f32_16x16x32_bf16 v[174:177], v[218:221], v[166:169], v[174:177]
	ds_read_b128 v[166:169], v6 offset:9216
	v_mfma_f32_16x16x32_bf16 v[64:67], v[214:217], v[178:181], v[64:67]
	v_mfma_f32_16x16x32_bf16 v[170:173], v[218:221], v[178:181], v[170:173]
	ds_read_b128 v[178:181], v6 offset:11264
	v_mfma_f32_16x16x32_bf16 v[80:83], v[214:217], v[222:225], v[80:83]
	v_mfma_f32_16x16x32_bf16 v[32:35], v[218:221], v[222:225], v[32:35]
	ds_read_b128 v[222:225], v6 offset:13312
	s_waitcnt lgkmcnt(3)
	v_mfma_f32_16x16x32_bf16 v[88:91], v[158:161], v[226:229], v[88:91]
	v_mfma_f32_16x16x32_bf16 v[92:95], v[162:165], v[226:229], v[92:95]
	v_mfma_f32_16x16x32_bf16 v[96:99], v[214:217], v[226:229], v[96:99]
	v_mfma_f32_16x16x32_bf16 v[36:39], v[218:221], v[226:229], v[36:39]
	ds_read_b128 v[226:229], v6 offset:15360
	s_waitcnt lgkmcnt(3)
	v_mfma_f32_16x16x32_bf16 v[104:107], v[158:161], v[166:169], v[104:107]
	v_mfma_f32_16x16x32_bf16 v[108:111], v[162:165], v[166:169], v[108:111]
	v_mfma_f32_16x16x32_bf16 v[112:115], v[214:217], v[166:169], v[112:115]
	v_mfma_f32_16x16x32_bf16 v[52:55], v[218:221], v[166:169], v[52:55]
	s_waitcnt lgkmcnt(2)
	v_mfma_f32_16x16x32_bf16 v[116:119], v[158:161], v[178:181], v[116:119]
	v_mfma_f32_16x16x32_bf16 v[120:123], v[162:165], v[178:181], v[120:123]
	v_mfma_f32_16x16x32_bf16 v[124:127], v[214:217], v[178:181], v[124:127]
	v_mfma_f32_16x16x32_bf16 v[68:71], v[218:221], v[178:181], v[68:71]
	s_waitcnt lgkmcnt(1)
	v_mfma_f32_16x16x32_bf16 v[128:131], v[158:161], v[222:225], v[128:131]
	v_mfma_f32_16x16x32_bf16 v[132:135], v[162:165], v[222:225], v[132:135]
	v_mfma_f32_16x16x32_bf16 v[136:139], v[214:217], v[222:225], v[136:139]
	v_mfma_f32_16x16x32_bf16 v[84:87], v[218:221], v[222:225], v[84:87]
	s_waitcnt lgkmcnt(0)
	v_mfma_f32_16x16x32_bf16 v[100:103], v[158:161], v[226:229], v[100:103]
	v_mfma_f32_16x16x32_bf16 v[140:143], v[162:165], v[226:229], v[140:143]
	v_mfma_f32_16x16x32_bf16 v[150:153], v[214:217], v[226:229], v[150:153]
	v_mfma_f32_16x16x32_bf16 v[154:157], v[218:221], v[226:229], v[154:157]
	s_add_u32 s46, s16, 0xa00
	s_addc_u32 s47, s17, 0
	s_add_u32 s48, s18, 0xa00
	s_waitcnt vmcnt(0)
	s_barrier
	s_addc_u32 s49, s19, 0
	ds_read_b128 v[158:161], v8
	ds_read_b128 v[162:165], v12
	ds_read_b128 v[166:169], v9
	ds_read_b128 v[178:181], v13
	ds_read_b128 v[214:217], v11
	ds_read_b128 v[218:221], v10
	ds_read_b128 v[222:225], v14
	ds_read_b128 v[226:229], v15
	s_waitcnt lgkmcnt(6)
	v_mfma_f32_16x16x32_bf16 v[40:43], v[158:161], v[162:165], v[40:43]
	s_waitcnt lgkmcnt(5)
	v_mfma_f32_16x16x32_bf16 v[44:47], v[166:169], v[162:165], v[44:47]
	s_waitcnt lgkmcnt(4)
	v_mfma_f32_16x16x32_bf16 v[56:59], v[158:161], v[178:181], v[56:59]
	s_mov_b32 m0, s1
	v_mfma_f32_16x16x32_bf16 v[60:63], v[166:169], v[178:181], v[60:63]
	global_load_lds_dwordx4 v0, s[46:47]
	s_waitcnt lgkmcnt(3)
	v_mfma_f32_16x16x32_bf16 v[48:51], v[214:217], v[162:165], v[48:51]
	v_mfma_f32_16x16x32_bf16 v[64:67], v[214:217], v[178:181], v[64:67]
	s_waitcnt lgkmcnt(2)
	v_mfma_f32_16x16x32_bf16 v[174:177], v[218:221], v[162:165], v[174:177]
	ds_read_b128 v[162:165], v16
	v_mfma_f32_16x16x32_bf16 v[170:173], v[218:221], v[178:181], v[170:173]
	ds_read_b128 v[178:181], v17
	s_waitcnt lgkmcnt(3)
	s_mov_b32 m0, s30
	v_mfma_f32_16x16x32_bf16 v[72:75], v[158:161], v[222:225], v[72:75]
	global_load_lds_dwordx4 v0, s[48:49]
	v_mfma_f32_16x16x32_bf16 v[76:79], v[166:169], v[222:225], v[76:79]
	v_mfma_f32_16x16x32_bf16 v[80:83], v[214:217], v[222:225], v[80:83]
	v_mfma_f32_16x16x32_bf16 v[32:35], v[218:221], v[222:225], v[32:35]
	ds_read_b128 v[222:225], v18
	s_waitcnt lgkmcnt(3)
	v_mfma_f32_16x16x32_bf16 v[88:91], v[158:161], v[226:229], v[88:91]
	s_mov_b32 m0, s31
	v_mfma_f32_16x16x32_bf16 v[92:95], v[166:169], v[226:229], v[92:95]
	global_load_lds_dwordx4 v2, s[46:47]
	v_mfma_f32_16x16x32_bf16 v[96:99], v[214:217], v[226:229], v[96:99]
	v_mfma_f32_16x16x32_bf16 v[36:39], v[218:221], v[226:229], v[36:39]
	ds_read_b128 v[226:229], v19
	s_waitcnt lgkmcnt(3)
	v_mfma_f32_16x16x32_bf16 v[104:107], v[158:161], v[162:165], v[104:107]
	s_waitcnt lgkmcnt(2)
	v_mfma_f32_16x16x32_bf16 v[116:119], v[158:161], v[178:181], v[116:119]
	s_waitcnt lgkmcnt(1)
	s_mov_b32 m0, s34
	v_mfma_f32_16x16x32_bf16 v[128:131], v[158:161], v[222:225], v[128:131]
	global_load_lds_dwordx4 v2, s[48:49]
	s_waitcnt lgkmcnt(0)
	v_mfma_f32_16x16x32_bf16 v[100:103], v[158:161], v[226:229], v[100:103]
	ds_read_b128 v[158:161], v20
	v_mfma_f32_16x16x32_bf16 v[108:111], v[166:169], v[162:165], v[108:111]
	v_mfma_f32_16x16x32_bf16 v[120:123], v[166:169], v[178:181], v[120:123]
	v_mfma_f32_16x16x32_bf16 v[132:135], v[166:169], v[222:225], v[132:135]
	s_mov_b32 m0, s35
	v_mfma_f32_16x16x32_bf16 v[140:143], v[166:169], v[226:229], v[140:143]
	global_load_lds_dwordx4 v4, s[46:47]
	ds_read_b128 v[166:169], v24
	v_mfma_f32_16x16x32_bf16 v[112:115], v[214:217], v[162:165], v[112:115]
	v_mfma_f32_16x16x32_bf16 v[52:55], v[218:221], v[162:165], v[52:55]
	ds_read_b128 v[162:165], v21
	v_mfma_f32_16x16x32_bf16 v[124:127], v[214:217], v[178:181], v[124:127]
	v_mfma_f32_16x16x32_bf16 v[68:71], v[218:221], v[178:181], v[68:71]
	ds_read_b128 v[178:181], v25
	s_mov_b32 m0, s36
	v_mfma_f32_16x16x32_bf16 v[136:139], v[214:217], v[222:225], v[136:139]
	global_load_lds_dwordx4 v4, s[48:49]
	v_mfma_f32_16x16x32_bf16 v[84:87], v[218:221], v[222:225], v[84:87]
	ds_read_b128 v[222:225], v26
	v_mfma_f32_16x16x32_bf16 v[150:153], v[214:217], v[226:229], v[150:153]
	ds_read_b128 v[214:217], v23
	v_mfma_f32_16x16x32_bf16 v[154:157], v[218:221], v[226:229], v[154:157]
	ds_read_b128 v[218:221], v22
	ds_read_b128 v[226:229], v27
	s_waitcnt lgkmcnt(6)
	v_mfma_f32_16x16x32_bf16 v[40:43], v[158:161], v[166:169], v[40:43]
	s_waitcnt lgkmcnt(5)
	s_mov_b32 m0, s37
	v_mfma_f32_16x16x32_bf16 v[44:47], v[162:165], v[166:169], v[44:47]
	global_load_lds_dwordx4 v146, s[46:47]
	s_waitcnt lgkmcnt(4)
	v_mfma_f32_16x16x32_bf16 v[56:59], v[158:161], v[178:181], v[56:59]
	v_mfma_f32_16x16x32_bf16 v[60:63], v[162:165], v[178:181], v[60:63]
	s_waitcnt lgkmcnt(3)
	v_mfma_f32_16x16x32_bf16 v[72:75], v[158:161], v[222:225], v[72:75]
	v_mfma_f32_16x16x32_bf16 v[76:79], v[162:165], v[222:225], v[76:79]
	s_waitcnt lgkmcnt(2)
	s_mov_b32 m0, s38
	v_mfma_f32_16x16x32_bf16 v[48:51], v[214:217], v[166:169], v[48:51]
	global_load_lds_dwordx4 v146, s[48:49]
	s_waitcnt lgkmcnt(1)
	v_mfma_f32_16x16x32_bf16 v[174:177], v[218:221], v[166:169], v[174:177]
	ds_read_b128 v[166:169], v28
	v_mfma_f32_16x16x32_bf16 v[64:67], v[214:217], v[178:181], v[64:67]
	v_mfma_f32_16x16x32_bf16 v[170:173], v[218:221], v[178:181], v[170:173]
	ds_read_b128 v[178:181], v29
	v_mfma_f32_16x16x32_bf16 v[80:83], v[214:217], v[222:225], v[80:83]
	v_mfma_f32_16x16x32_bf16 v[32:35], v[218:221], v[222:225], v[32:35]
	ds_read_b128 v[222:225], v30
	s_waitcnt lgkmcnt(3)
	v_mfma_f32_16x16x32_bf16 v[88:91], v[158:161], v[226:229], v[88:91]
	v_mfma_f32_16x16x32_bf16 v[92:95], v[162:165], v[226:229], v[92:95]
	v_mfma_f32_16x16x32_bf16 v[96:99], v[214:217], v[226:229], v[96:99]
	v_mfma_f32_16x16x32_bf16 v[36:39], v[218:221], v[226:229], v[36:39]
	ds_read_b128 v[226:229], v31
	s_waitcnt lgkmcnt(3)
	v_mfma_f32_16x16x32_bf16 v[104:107], v[158:161], v[166:169], v[104:107]
	v_mfma_f32_16x16x32_bf16 v[108:111], v[162:165], v[166:169], v[108:111]
	v_mfma_f32_16x16x32_bf16 v[112:115], v[214:217], v[166:169], v[112:115]
	v_mfma_f32_16x16x32_bf16 v[52:55], v[218:221], v[166:169], v[52:55]
	s_waitcnt lgkmcnt(2)
	v_mfma_f32_16x16x32_bf16 v[116:119], v[158:161], v[178:181], v[116:119]
	v_mfma_f32_16x16x32_bf16 v[120:123], v[162:165], v[178:181], v[120:123]
	v_mfma_f32_16x16x32_bf16 v[124:127], v[214:217], v[178:181], v[124:127]
	v_mfma_f32_16x16x32_bf16 v[68:71], v[218:221], v[178:181], v[68:71]
	s_waitcnt lgkmcnt(1)
	v_mfma_f32_16x16x32_bf16 v[128:131], v[158:161], v[222:225], v[128:131]
	v_mfma_f32_16x16x32_bf16 v[132:135], v[162:165], v[222:225], v[132:135]
	v_mfma_f32_16x16x32_bf16 v[136:139], v[214:217], v[222:225], v[136:139]
	v_mfma_f32_16x16x32_bf16 v[84:87], v[218:221], v[222:225], v[84:87]
	s_waitcnt lgkmcnt(0)
	v_mfma_f32_16x16x32_bf16 v[100:103], v[158:161], v[226:229], v[100:103]
	v_mfma_f32_16x16x32_bf16 v[140:143], v[162:165], v[226:229], v[140:143]
	v_mfma_f32_16x16x32_bf16 v[150:153], v[214:217], v[226:229], v[150:153]
	v_mfma_f32_16x16x32_bf16 v[154:157], v[218:221], v[226:229], v[154:157]
	s_add_u32 s46, s16, 0xa80
	s_addc_u32 s47, s17, 0
	s_add_u32 s48, s18, 0xa80
	s_waitcnt vmcnt(0)
	s_barrier
	s_addc_u32 s49, s19, 0
	ds_read_b128 v[158:161], v7 offset:32768
	ds_read_b128 v[162:165], v6
	ds_read_b128 v[166:169], v7 offset:34816
	ds_read_b128 v[178:181], v6 offset:2048
	ds_read_b128 v[214:217], v7 offset:36864
	ds_read_b128 v[218:221], v7 offset:38912
	ds_read_b128 v[222:225], v6 offset:4096
	ds_read_b128 v[226:229], v6 offset:6144
	s_waitcnt lgkmcnt(6)
	v_mfma_f32_16x16x32_bf16 v[40:43], v[158:161], v[162:165], v[40:43]
	s_waitcnt lgkmcnt(5)
	v_mfma_f32_16x16x32_bf16 v[44:47], v[166:169], v[162:165], v[44:47]
	s_waitcnt lgkmcnt(4)
	v_mfma_f32_16x16x32_bf16 v[56:59], v[158:161], v[178:181], v[56:59]
	s_mov_b32 m0, s25
	v_mfma_f32_16x16x32_bf16 v[60:63], v[166:169], v[178:181], v[60:63]
	global_load_lds_dwordx4 v0, s[46:47]
	s_waitcnt lgkmcnt(3)
	v_mfma_f32_16x16x32_bf16 v[48:51], v[214:217], v[162:165], v[48:51]
	v_mfma_f32_16x16x32_bf16 v[64:67], v[214:217], v[178:181], v[64:67]
	s_waitcnt lgkmcnt(2)
	v_mfma_f32_16x16x32_bf16 v[174:177], v[218:221], v[162:165], v[174:177]
	ds_read_b128 v[162:165], v6 offset:8192
	v_mfma_f32_16x16x32_bf16 v[170:173], v[218:221], v[178:181], v[170:173]
	ds_read_b128 v[178:181], v6 offset:10240
	s_waitcnt lgkmcnt(3)
	s_mov_b32 m0, s24
	v_mfma_f32_16x16x32_bf16 v[72:75], v[158:161], v[222:225], v[72:75]
	global_load_lds_dwordx4 v0, s[48:49]
	v_mfma_f32_16x16x32_bf16 v[76:79], v[166:169], v[222:225], v[76:79]
	v_mfma_f32_16x16x32_bf16 v[80:83], v[214:217], v[222:225], v[80:83]
	v_mfma_f32_16x16x32_bf16 v[32:35], v[218:221], v[222:225], v[32:35]
	ds_read_b128 v[222:225], v6 offset:12288
	s_waitcnt lgkmcnt(3)
	v_mfma_f32_16x16x32_bf16 v[88:91], v[158:161], v[226:229], v[88:91]
	s_mov_b32 m0, s39
	v_mfma_f32_16x16x32_bf16 v[92:95], v[166:169], v[226:229], v[92:95]
	global_load_lds_dwordx4 v2, s[46:47]
	v_mfma_f32_16x16x32_bf16 v[96:99], v[214:217], v[226:229], v[96:99]
	v_mfma_f32_16x16x32_bf16 v[36:39], v[218:221], v[226:229], v[36:39]
	ds_read_b128 v[226:229], v6 offset:14336
	s_waitcnt lgkmcnt(3)
	v_mfma_f32_16x16x32_bf16 v[104:107], v[158:161], v[162:165], v[104:107]
	s_waitcnt lgkmcnt(2)
	v_mfma_f32_16x16x32_bf16 v[116:119], v[158:161], v[178:181], v[116:119]
	s_waitcnt lgkmcnt(1)
	s_mov_b32 m0, s40
	v_mfma_f32_16x16x32_bf16 v[128:131], v[158:161], v[222:225], v[128:131]
	global_load_lds_dwordx4 v2, s[48:49]
	s_waitcnt lgkmcnt(0)
	v_mfma_f32_16x16x32_bf16 v[100:103], v[158:161], v[226:229], v[100:103]
	ds_read_b128 v[158:161], v7 offset:33792
	v_mfma_f32_16x16x32_bf16 v[108:111], v[166:169], v[162:165], v[108:111]
	v_mfma_f32_16x16x32_bf16 v[120:123], v[166:169], v[178:181], v[120:123]
	v_mfma_f32_16x16x32_bf16 v[132:135], v[166:169], v[222:225], v[132:135]
	s_mov_b32 m0, s41
	v_mfma_f32_16x16x32_bf16 v[140:143], v[166:169], v[226:229], v[140:143]
	global_load_lds_dwordx4 v4, s[46:47]
	ds_read_b128 v[166:169], v6 offset:1024
	v_mfma_f32_16x16x32_bf16 v[112:115], v[214:217], v[162:165], v[112:115]
	v_mfma_f32_16x16x32_bf16 v[52:55], v[218:221], v[162:165], v[52:55]
	ds_read_b128 v[162:165], v7 offset:35840
	v_mfma_f32_16x16x32_bf16 v[124:127], v[214:217], v[178:181], v[124:127]
	v_mfma_f32_16x16x32_bf16 v[68:71], v[218:221], v[178:181], v[68:71]
	ds_read_b128 v[178:181], v6 offset:3072
	s_mov_b32 m0, s42
	v_mfma_f32_16x16x32_bf16 v[136:139], v[214:217], v[222:225], v[136:139]
	global_load_lds_dwordx4 v4, s[48:49]
	v_mfma_f32_16x16x32_bf16 v[84:87], v[218:221], v[222:225], v[84:87]
	ds_read_b128 v[222:225], v6 offset:5120
	v_mfma_f32_16x16x32_bf16 v[150:153], v[214:217], v[226:229], v[150:153]
	ds_read_b128 v[214:217], v7 offset:37888
	v_mfma_f32_16x16x32_bf16 v[154:157], v[218:221], v[226:229], v[154:157]
	ds_read_b128 v[218:221], v7 offset:39936
	ds_read_b128 v[226:229], v6 offset:7168
	s_waitcnt lgkmcnt(6)
	v_mfma_f32_16x16x32_bf16 v[40:43], v[158:161], v[166:169], v[40:43]
	s_waitcnt lgkmcnt(5)
	s_mov_b32 m0, s43
	v_mfma_f32_16x16x32_bf16 v[44:47], v[162:165], v[166:169], v[44:47]
	global_load_lds_dwordx4 v146, s[46:47]
	s_waitcnt lgkmcnt(4)
	v_mfma_f32_16x16x32_bf16 v[56:59], v[158:161], v[178:181], v[56:59]
	v_mfma_f32_16x16x32_bf16 v[60:63], v[162:165], v[178:181], v[60:63]
	s_waitcnt lgkmcnt(3)
	v_mfma_f32_16x16x32_bf16 v[72:75], v[158:161], v[222:225], v[72:75]
	v_mfma_f32_16x16x32_bf16 v[76:79], v[162:165], v[222:225], v[76:79]
	s_waitcnt lgkmcnt(2)
	s_mov_b32 m0, s44
	v_mfma_f32_16x16x32_bf16 v[48:51], v[214:217], v[166:169], v[48:51]
	global_load_lds_dwordx4 v146, s[48:49]
	s_waitcnt lgkmcnt(1)
	v_mfma_f32_16x16x32_bf16 v[174:177], v[218:221], v[166:169], v[174:177]
	ds_read_b128 v[166:169], v6 offset:9216
	v_mfma_f32_16x16x32_bf16 v[64:67], v[214:217], v[178:181], v[64:67]
	v_mfma_f32_16x16x32_bf16 v[170:173], v[218:221], v[178:181], v[170:173]
	ds_read_b128 v[178:181], v6 offset:11264
	v_mfma_f32_16x16x32_bf16 v[80:83], v[214:217], v[222:225], v[80:83]
	v_mfma_f32_16x16x32_bf16 v[32:35], v[218:221], v[222:225], v[32:35]
	ds_read_b128 v[222:225], v6 offset:13312
	s_waitcnt lgkmcnt(3)
	v_mfma_f32_16x16x32_bf16 v[88:91], v[158:161], v[226:229], v[88:91]
	v_mfma_f32_16x16x32_bf16 v[92:95], v[162:165], v[226:229], v[92:95]
	v_mfma_f32_16x16x32_bf16 v[96:99], v[214:217], v[226:229], v[96:99]
	v_mfma_f32_16x16x32_bf16 v[36:39], v[218:221], v[226:229], v[36:39]
	ds_read_b128 v[226:229], v6 offset:15360
	s_waitcnt lgkmcnt(3)
	v_mfma_f32_16x16x32_bf16 v[104:107], v[158:161], v[166:169], v[104:107]
	v_mfma_f32_16x16x32_bf16 v[108:111], v[162:165], v[166:169], v[108:111]
	v_mfma_f32_16x16x32_bf16 v[112:115], v[214:217], v[166:169], v[112:115]
	v_mfma_f32_16x16x32_bf16 v[52:55], v[218:221], v[166:169], v[52:55]
	s_waitcnt lgkmcnt(2)
	v_mfma_f32_16x16x32_bf16 v[116:119], v[158:161], v[178:181], v[116:119]
	v_mfma_f32_16x16x32_bf16 v[120:123], v[162:165], v[178:181], v[120:123]
	v_mfma_f32_16x16x32_bf16 v[124:127], v[214:217], v[178:181], v[124:127]
	v_mfma_f32_16x16x32_bf16 v[68:71], v[218:221], v[178:181], v[68:71]
	s_waitcnt lgkmcnt(1)
	v_mfma_f32_16x16x32_bf16 v[128:131], v[158:161], v[222:225], v[128:131]
	v_mfma_f32_16x16x32_bf16 v[132:135], v[162:165], v[222:225], v[132:135]
	v_mfma_f32_16x16x32_bf16 v[136:139], v[214:217], v[222:225], v[136:139]
	v_mfma_f32_16x16x32_bf16 v[84:87], v[218:221], v[222:225], v[84:87]
	s_waitcnt lgkmcnt(0)
	v_mfma_f32_16x16x32_bf16 v[100:103], v[158:161], v[226:229], v[100:103]
	v_mfma_f32_16x16x32_bf16 v[140:143], v[162:165], v[226:229], v[140:143]
	v_mfma_f32_16x16x32_bf16 v[150:153], v[214:217], v[226:229], v[150:153]
	v_mfma_f32_16x16x32_bf16 v[154:157], v[218:221], v[226:229], v[154:157]
	s_add_u32 s46, s16, 0xb00
	s_addc_u32 s47, s17, 0
	s_add_u32 s48, s18, 0xb00
	s_waitcnt vmcnt(0)
	s_barrier
	s_addc_u32 s49, s19, 0
	ds_read_b128 v[158:161], v8
	ds_read_b128 v[162:165], v12
	ds_read_b128 v[166:169], v9
	ds_read_b128 v[178:181], v13
	ds_read_b128 v[214:217], v11
	ds_read_b128 v[218:221], v10
	ds_read_b128 v[222:225], v14
	ds_read_b128 v[226:229], v15
	s_waitcnt lgkmcnt(6)
	v_mfma_f32_16x16x32_bf16 v[40:43], v[158:161], v[162:165], v[40:43]
	s_waitcnt lgkmcnt(5)
	v_mfma_f32_16x16x32_bf16 v[44:47], v[166:169], v[162:165], v[44:47]
	s_waitcnt lgkmcnt(4)
	v_mfma_f32_16x16x32_bf16 v[56:59], v[158:161], v[178:181], v[56:59]
	s_mov_b32 m0, s1
	v_mfma_f32_16x16x32_bf16 v[60:63], v[166:169], v[178:181], v[60:63]
	global_load_lds_dwordx4 v0, s[46:47]
	s_waitcnt lgkmcnt(3)
	v_mfma_f32_16x16x32_bf16 v[48:51], v[214:217], v[162:165], v[48:51]
	v_mfma_f32_16x16x32_bf16 v[64:67], v[214:217], v[178:181], v[64:67]
	s_waitcnt lgkmcnt(2)
	v_mfma_f32_16x16x32_bf16 v[174:177], v[218:221], v[162:165], v[174:177]
	ds_read_b128 v[162:165], v16
	v_mfma_f32_16x16x32_bf16 v[170:173], v[218:221], v[178:181], v[170:173]
	ds_read_b128 v[178:181], v17
	s_waitcnt lgkmcnt(3)
	s_mov_b32 m0, s30
	v_mfma_f32_16x16x32_bf16 v[72:75], v[158:161], v[222:225], v[72:75]
	global_load_lds_dwordx4 v0, s[48:49]
	v_mfma_f32_16x16x32_bf16 v[76:79], v[166:169], v[222:225], v[76:79]
	v_mfma_f32_16x16x32_bf16 v[80:83], v[214:217], v[222:225], v[80:83]
	v_mfma_f32_16x16x32_bf16 v[32:35], v[218:221], v[222:225], v[32:35]
	ds_read_b128 v[222:225], v18
	s_waitcnt lgkmcnt(3)
	v_mfma_f32_16x16x32_bf16 v[88:91], v[158:161], v[226:229], v[88:91]
	s_mov_b32 m0, s31
	v_mfma_f32_16x16x32_bf16 v[92:95], v[166:169], v[226:229], v[92:95]
	global_load_lds_dwordx4 v2, s[46:47]
	v_mfma_f32_16x16x32_bf16 v[96:99], v[214:217], v[226:229], v[96:99]
	v_mfma_f32_16x16x32_bf16 v[36:39], v[218:221], v[226:229], v[36:39]
	ds_read_b128 v[226:229], v19
	s_waitcnt lgkmcnt(3)
	v_mfma_f32_16x16x32_bf16 v[104:107], v[158:161], v[162:165], v[104:107]
	s_waitcnt lgkmcnt(2)
	v_mfma_f32_16x16x32_bf16 v[116:119], v[158:161], v[178:181], v[116:119]
	s_waitcnt lgkmcnt(1)
	s_mov_b32 m0, s34
	v_mfma_f32_16x16x32_bf16 v[128:131], v[158:161], v[222:225], v[128:131]
	global_load_lds_dwordx4 v2, s[48:49]
	s_waitcnt lgkmcnt(0)
	v_mfma_f32_16x16x32_bf16 v[100:103], v[158:161], v[226:229], v[100:103]
	ds_read_b128 v[158:161], v20
	v_mfma_f32_16x16x32_bf16 v[108:111], v[166:169], v[162:165], v[108:111]
	v_mfma_f32_16x16x32_bf16 v[120:123], v[166:169], v[178:181], v[120:123]
	v_mfma_f32_16x16x32_bf16 v[132:135], v[166:169], v[222:225], v[132:135]
	s_mov_b32 m0, s35
	v_mfma_f32_16x16x32_bf16 v[140:143], v[166:169], v[226:229], v[140:143]
	global_load_lds_dwordx4 v4, s[46:47]
	ds_read_b128 v[166:169], v24
	v_mfma_f32_16x16x32_bf16 v[112:115], v[214:217], v[162:165], v[112:115]
	v_mfma_f32_16x16x32_bf16 v[52:55], v[218:221], v[162:165], v[52:55]
	ds_read_b128 v[162:165], v21
	v_mfma_f32_16x16x32_bf16 v[124:127], v[214:217], v[178:181], v[124:127]
	v_mfma_f32_16x16x32_bf16 v[68:71], v[218:221], v[178:181], v[68:71]
	ds_read_b128 v[178:181], v25
	s_mov_b32 m0, s36
	v_mfma_f32_16x16x32_bf16 v[136:139], v[214:217], v[222:225], v[136:139]
	global_load_lds_dwordx4 v4, s[48:49]
	v_mfma_f32_16x16x32_bf16 v[84:87], v[218:221], v[222:225], v[84:87]
	ds_read_b128 v[222:225], v26
	v_mfma_f32_16x16x32_bf16 v[150:153], v[214:217], v[226:229], v[150:153]
	ds_read_b128 v[214:217], v23
	v_mfma_f32_16x16x32_bf16 v[154:157], v[218:221], v[226:229], v[154:157]
	ds_read_b128 v[218:221], v22
	ds_read_b128 v[226:229], v27
	s_waitcnt lgkmcnt(6)
	v_mfma_f32_16x16x32_bf16 v[40:43], v[158:161], v[166:169], v[40:43]
	s_waitcnt lgkmcnt(5)
	s_mov_b32 m0, s37
	v_mfma_f32_16x16x32_bf16 v[44:47], v[162:165], v[166:169], v[44:47]
	global_load_lds_dwordx4 v146, s[46:47]
	s_waitcnt lgkmcnt(4)
	v_mfma_f32_16x16x32_bf16 v[56:59], v[158:161], v[178:181], v[56:59]
	v_mfma_f32_16x16x32_bf16 v[60:63], v[162:165], v[178:181], v[60:63]
	s_waitcnt lgkmcnt(3)
	v_mfma_f32_16x16x32_bf16 v[72:75], v[158:161], v[222:225], v[72:75]
	v_mfma_f32_16x16x32_bf16 v[76:79], v[162:165], v[222:225], v[76:79]
	s_waitcnt lgkmcnt(2)
	s_mov_b32 m0, s38
	v_mfma_f32_16x16x32_bf16 v[48:51], v[214:217], v[166:169], v[48:51]
	global_load_lds_dwordx4 v146, s[48:49]
	s_waitcnt lgkmcnt(1)
	v_mfma_f32_16x16x32_bf16 v[174:177], v[218:221], v[166:169], v[174:177]
	ds_read_b128 v[166:169], v28
	v_mfma_f32_16x16x32_bf16 v[64:67], v[214:217], v[178:181], v[64:67]
	v_mfma_f32_16x16x32_bf16 v[170:173], v[218:221], v[178:181], v[170:173]
	ds_read_b128 v[178:181], v29
	v_mfma_f32_16x16x32_bf16 v[80:83], v[214:217], v[222:225], v[80:83]
	v_mfma_f32_16x16x32_bf16 v[32:35], v[218:221], v[222:225], v[32:35]
	ds_read_b128 v[222:225], v30
	s_waitcnt lgkmcnt(3)
	v_mfma_f32_16x16x32_bf16 v[88:91], v[158:161], v[226:229], v[88:91]
	v_mfma_f32_16x16x32_bf16 v[92:95], v[162:165], v[226:229], v[92:95]
	v_mfma_f32_16x16x32_bf16 v[96:99], v[214:217], v[226:229], v[96:99]
	v_mfma_f32_16x16x32_bf16 v[36:39], v[218:221], v[226:229], v[36:39]
	ds_read_b128 v[226:229], v31
	s_waitcnt lgkmcnt(3)
	v_mfma_f32_16x16x32_bf16 v[104:107], v[158:161], v[166:169], v[104:107]
	v_mfma_f32_16x16x32_bf16 v[108:111], v[162:165], v[166:169], v[108:111]
	v_mfma_f32_16x16x32_bf16 v[112:115], v[214:217], v[166:169], v[112:115]
	v_mfma_f32_16x16x32_bf16 v[52:55], v[218:221], v[166:169], v[52:55]
	s_waitcnt lgkmcnt(2)
	v_mfma_f32_16x16x32_bf16 v[116:119], v[158:161], v[178:181], v[116:119]
	v_mfma_f32_16x16x32_bf16 v[120:123], v[162:165], v[178:181], v[120:123]
	v_mfma_f32_16x16x32_bf16 v[124:127], v[214:217], v[178:181], v[124:127]
	v_mfma_f32_16x16x32_bf16 v[68:71], v[218:221], v[178:181], v[68:71]
	s_waitcnt lgkmcnt(1)
	v_mfma_f32_16x16x32_bf16 v[128:131], v[158:161], v[222:225], v[128:131]
	v_mfma_f32_16x16x32_bf16 v[132:135], v[162:165], v[222:225], v[132:135]
	v_mfma_f32_16x16x32_bf16 v[136:139], v[214:217], v[222:225], v[136:139]
	v_mfma_f32_16x16x32_bf16 v[84:87], v[218:221], v[222:225], v[84:87]
	s_waitcnt lgkmcnt(0)
	v_mfma_f32_16x16x32_bf16 v[100:103], v[158:161], v[226:229], v[100:103]
	v_mfma_f32_16x16x32_bf16 v[140:143], v[162:165], v[226:229], v[140:143]
	v_mfma_f32_16x16x32_bf16 v[150:153], v[214:217], v[226:229], v[150:153]
	v_mfma_f32_16x16x32_bf16 v[154:157], v[218:221], v[226:229], v[154:157]
	s_add_u32 s46, s16, 0xb80
	s_addc_u32 s47, s17, 0
	s_add_u32 s48, s18, 0xb80
	s_waitcnt vmcnt(0)
	s_barrier
	s_addc_u32 s49, s19, 0
	ds_read_b128 v[158:161], v7 offset:32768
	ds_read_b128 v[162:165], v6
	ds_read_b128 v[166:169], v7 offset:34816
	ds_read_b128 v[178:181], v6 offset:2048
	ds_read_b128 v[214:217], v7 offset:36864
	ds_read_b128 v[218:221], v7 offset:38912
	ds_read_b128 v[222:225], v6 offset:4096
	ds_read_b128 v[226:229], v6 offset:6144
	s_waitcnt lgkmcnt(6)
	v_mfma_f32_16x16x32_bf16 v[40:43], v[158:161], v[162:165], v[40:43]
	s_waitcnt lgkmcnt(5)
	v_mfma_f32_16x16x32_bf16 v[44:47], v[166:169], v[162:165], v[44:47]
	s_waitcnt lgkmcnt(4)
	v_mfma_f32_16x16x32_bf16 v[56:59], v[158:161], v[178:181], v[56:59]
	s_mov_b32 m0, s25
	v_mfma_f32_16x16x32_bf16 v[60:63], v[166:169], v[178:181], v[60:63]
	global_load_lds_dwordx4 v0, s[46:47]
	s_waitcnt lgkmcnt(3)
	v_mfma_f32_16x16x32_bf16 v[48:51], v[214:217], v[162:165], v[48:51]
	v_mfma_f32_16x16x32_bf16 v[64:67], v[214:217], v[178:181], v[64:67]
	s_waitcnt lgkmcnt(2)
	v_mfma_f32_16x16x32_bf16 v[174:177], v[218:221], v[162:165], v[174:177]
	ds_read_b128 v[162:165], v6 offset:8192
	v_mfma_f32_16x16x32_bf16 v[170:173], v[218:221], v[178:181], v[170:173]
	ds_read_b128 v[178:181], v6 offset:10240
	s_waitcnt lgkmcnt(3)
	s_mov_b32 m0, s24
	v_mfma_f32_16x16x32_bf16 v[72:75], v[158:161], v[222:225], v[72:75]
	global_load_lds_dwordx4 v0, s[48:49]
	v_mfma_f32_16x16x32_bf16 v[76:79], v[166:169], v[222:225], v[76:79]
	v_mfma_f32_16x16x32_bf16 v[80:83], v[214:217], v[222:225], v[80:83]
	v_mfma_f32_16x16x32_bf16 v[32:35], v[218:221], v[222:225], v[32:35]
	ds_read_b128 v[222:225], v6 offset:12288
	s_waitcnt lgkmcnt(3)
	v_mfma_f32_16x16x32_bf16 v[88:91], v[158:161], v[226:229], v[88:91]
	s_mov_b32 m0, s39
	v_mfma_f32_16x16x32_bf16 v[92:95], v[166:169], v[226:229], v[92:95]
	global_load_lds_dwordx4 v2, s[46:47]
	v_mfma_f32_16x16x32_bf16 v[96:99], v[214:217], v[226:229], v[96:99]
	v_mfma_f32_16x16x32_bf16 v[36:39], v[218:221], v[226:229], v[36:39]
	ds_read_b128 v[226:229], v6 offset:14336
	s_waitcnt lgkmcnt(3)
	v_mfma_f32_16x16x32_bf16 v[104:107], v[158:161], v[162:165], v[104:107]
	s_waitcnt lgkmcnt(2)
	v_mfma_f32_16x16x32_bf16 v[116:119], v[158:161], v[178:181], v[116:119]
	s_waitcnt lgkmcnt(1)
	s_mov_b32 m0, s40
	v_mfma_f32_16x16x32_bf16 v[128:131], v[158:161], v[222:225], v[128:131]
	global_load_lds_dwordx4 v2, s[48:49]
	s_waitcnt lgkmcnt(0)
	v_mfma_f32_16x16x32_bf16 v[100:103], v[158:161], v[226:229], v[100:103]
	ds_read_b128 v[158:161], v7 offset:33792
	v_mfma_f32_16x16x32_bf16 v[108:111], v[166:169], v[162:165], v[108:111]
	v_mfma_f32_16x16x32_bf16 v[120:123], v[166:169], v[178:181], v[120:123]
	v_mfma_f32_16x16x32_bf16 v[132:135], v[166:169], v[222:225], v[132:135]
	s_mov_b32 m0, s41
	v_mfma_f32_16x16x32_bf16 v[140:143], v[166:169], v[226:229], v[140:143]
	global_load_lds_dwordx4 v4, s[46:47]
	ds_read_b128 v[166:169], v6 offset:1024
	v_mfma_f32_16x16x32_bf16 v[112:115], v[214:217], v[162:165], v[112:115]
	v_mfma_f32_16x16x32_bf16 v[52:55], v[218:221], v[162:165], v[52:55]
	ds_read_b128 v[162:165], v7 offset:35840
	v_mfma_f32_16x16x32_bf16 v[124:127], v[214:217], v[178:181], v[124:127]
	v_mfma_f32_16x16x32_bf16 v[68:71], v[218:221], v[178:181], v[68:71]
	ds_read_b128 v[178:181], v6 offset:3072
	s_mov_b32 m0, s42
	v_mfma_f32_16x16x32_bf16 v[136:139], v[214:217], v[222:225], v[136:139]
	global_load_lds_dwordx4 v4, s[48:49]
	v_mfma_f32_16x16x32_bf16 v[84:87], v[218:221], v[222:225], v[84:87]
	ds_read_b128 v[222:225], v6 offset:5120
	v_mfma_f32_16x16x32_bf16 v[150:153], v[214:217], v[226:229], v[150:153]
	ds_read_b128 v[214:217], v7 offset:37888
	v_mfma_f32_16x16x32_bf16 v[154:157], v[218:221], v[226:229], v[154:157]
	ds_read_b128 v[218:221], v7 offset:39936
	ds_read_b128 v[226:229], v6 offset:7168
	s_waitcnt lgkmcnt(6)
	v_mfma_f32_16x16x32_bf16 v[40:43], v[158:161], v[166:169], v[40:43]
	s_waitcnt lgkmcnt(5)
	s_mov_b32 m0, s43
	v_mfma_f32_16x16x32_bf16 v[44:47], v[162:165], v[166:169], v[44:47]
	global_load_lds_dwordx4 v146, s[46:47]
	s_waitcnt lgkmcnt(4)
	v_mfma_f32_16x16x32_bf16 v[56:59], v[158:161], v[178:181], v[56:59]
	v_mfma_f32_16x16x32_bf16 v[60:63], v[162:165], v[178:181], v[60:63]
	s_waitcnt lgkmcnt(3)
	v_mfma_f32_16x16x32_bf16 v[72:75], v[158:161], v[222:225], v[72:75]
	v_mfma_f32_16x16x32_bf16 v[76:79], v[162:165], v[222:225], v[76:79]
	s_waitcnt lgkmcnt(2)
	s_mov_b32 m0, s44
	v_mfma_f32_16x16x32_bf16 v[48:51], v[214:217], v[166:169], v[48:51]
	global_load_lds_dwordx4 v146, s[48:49]
	s_waitcnt lgkmcnt(1)
	v_mfma_f32_16x16x32_bf16 v[174:177], v[218:221], v[166:169], v[174:177]
	ds_read_b128 v[166:169], v6 offset:9216
	v_mfma_f32_16x16x32_bf16 v[64:67], v[214:217], v[178:181], v[64:67]
	v_mfma_f32_16x16x32_bf16 v[170:173], v[218:221], v[178:181], v[170:173]
	ds_read_b128 v[178:181], v6 offset:11264
	v_mfma_f32_16x16x32_bf16 v[80:83], v[214:217], v[222:225], v[80:83]
	v_mfma_f32_16x16x32_bf16 v[32:35], v[218:221], v[222:225], v[32:35]
	ds_read_b128 v[222:225], v6 offset:13312
	s_waitcnt lgkmcnt(3)
	v_mfma_f32_16x16x32_bf16 v[88:91], v[158:161], v[226:229], v[88:91]
	v_mfma_f32_16x16x32_bf16 v[92:95], v[162:165], v[226:229], v[92:95]
	v_mfma_f32_16x16x32_bf16 v[96:99], v[214:217], v[226:229], v[96:99]
	v_mfma_f32_16x16x32_bf16 v[36:39], v[218:221], v[226:229], v[36:39]
	ds_read_b128 v[226:229], v6 offset:15360
	s_waitcnt lgkmcnt(3)
	v_mfma_f32_16x16x32_bf16 v[104:107], v[158:161], v[166:169], v[104:107]
	v_mfma_f32_16x16x32_bf16 v[108:111], v[162:165], v[166:169], v[108:111]
	v_mfma_f32_16x16x32_bf16 v[112:115], v[214:217], v[166:169], v[112:115]
	v_mfma_f32_16x16x32_bf16 v[52:55], v[218:221], v[166:169], v[52:55]
	s_waitcnt lgkmcnt(2)
	v_mfma_f32_16x16x32_bf16 v[116:119], v[158:161], v[178:181], v[116:119]
	v_mfma_f32_16x16x32_bf16 v[120:123], v[162:165], v[178:181], v[120:123]
	v_mfma_f32_16x16x32_bf16 v[124:127], v[214:217], v[178:181], v[124:127]
	v_mfma_f32_16x16x32_bf16 v[68:71], v[218:221], v[178:181], v[68:71]
	s_waitcnt lgkmcnt(1)
	v_mfma_f32_16x16x32_bf16 v[128:131], v[158:161], v[222:225], v[128:131]
	v_mfma_f32_16x16x32_bf16 v[132:135], v[162:165], v[222:225], v[132:135]
	v_mfma_f32_16x16x32_bf16 v[136:139], v[214:217], v[222:225], v[136:139]
	v_mfma_f32_16x16x32_bf16 v[84:87], v[218:221], v[222:225], v[84:87]
	s_waitcnt lgkmcnt(0)
	v_mfma_f32_16x16x32_bf16 v[100:103], v[158:161], v[226:229], v[100:103]
	v_mfma_f32_16x16x32_bf16 v[140:143], v[162:165], v[226:229], v[140:143]
	v_mfma_f32_16x16x32_bf16 v[150:153], v[214:217], v[226:229], v[150:153]
	v_mfma_f32_16x16x32_bf16 v[154:157], v[218:221], v[226:229], v[154:157]
	s_add_u32 s46, s16, 0xc00
	s_addc_u32 s47, s17, 0
	s_add_u32 s48, s18, 0xc00
	s_waitcnt vmcnt(0)
	s_barrier
	s_addc_u32 s49, s19, 0
	ds_read_b128 v[158:161], v8
	ds_read_b128 v[162:165], v12
	ds_read_b128 v[166:169], v9
	ds_read_b128 v[178:181], v13
	ds_read_b128 v[214:217], v11
	ds_read_b128 v[218:221], v10
	ds_read_b128 v[222:225], v14
	ds_read_b128 v[226:229], v15
	s_waitcnt lgkmcnt(6)
	v_mfma_f32_16x16x32_bf16 v[40:43], v[158:161], v[162:165], v[40:43]
	s_waitcnt lgkmcnt(5)
	v_mfma_f32_16x16x32_bf16 v[44:47], v[166:169], v[162:165], v[44:47]
	s_waitcnt lgkmcnt(4)
	v_mfma_f32_16x16x32_bf16 v[56:59], v[158:161], v[178:181], v[56:59]
	s_mov_b32 m0, s1
	v_mfma_f32_16x16x32_bf16 v[60:63], v[166:169], v[178:181], v[60:63]
	global_load_lds_dwordx4 v0, s[46:47]
	s_waitcnt lgkmcnt(3)
	v_mfma_f32_16x16x32_bf16 v[48:51], v[214:217], v[162:165], v[48:51]
	v_mfma_f32_16x16x32_bf16 v[64:67], v[214:217], v[178:181], v[64:67]
	s_waitcnt lgkmcnt(2)
	v_mfma_f32_16x16x32_bf16 v[174:177], v[218:221], v[162:165], v[174:177]
	ds_read_b128 v[162:165], v16
	v_mfma_f32_16x16x32_bf16 v[170:173], v[218:221], v[178:181], v[170:173]
	ds_read_b128 v[178:181], v17
	s_waitcnt lgkmcnt(3)
	s_mov_b32 m0, s30
	v_mfma_f32_16x16x32_bf16 v[72:75], v[158:161], v[222:225], v[72:75]
	global_load_lds_dwordx4 v0, s[48:49]
	v_mfma_f32_16x16x32_bf16 v[76:79], v[166:169], v[222:225], v[76:79]
	v_mfma_f32_16x16x32_bf16 v[80:83], v[214:217], v[222:225], v[80:83]
	v_mfma_f32_16x16x32_bf16 v[32:35], v[218:221], v[222:225], v[32:35]
	ds_read_b128 v[222:225], v18
	s_waitcnt lgkmcnt(3)
	v_mfma_f32_16x16x32_bf16 v[88:91], v[158:161], v[226:229], v[88:91]
	s_mov_b32 m0, s31
	v_mfma_f32_16x16x32_bf16 v[92:95], v[166:169], v[226:229], v[92:95]
	global_load_lds_dwordx4 v2, s[46:47]
	v_mfma_f32_16x16x32_bf16 v[96:99], v[214:217], v[226:229], v[96:99]
	v_mfma_f32_16x16x32_bf16 v[36:39], v[218:221], v[226:229], v[36:39]
	ds_read_b128 v[226:229], v19
	s_waitcnt lgkmcnt(3)
	v_mfma_f32_16x16x32_bf16 v[104:107], v[158:161], v[162:165], v[104:107]
	s_waitcnt lgkmcnt(2)
	v_mfma_f32_16x16x32_bf16 v[116:119], v[158:161], v[178:181], v[116:119]
	s_waitcnt lgkmcnt(1)
	s_mov_b32 m0, s34
	v_mfma_f32_16x16x32_bf16 v[128:131], v[158:161], v[222:225], v[128:131]
	global_load_lds_dwordx4 v2, s[48:49]
	s_waitcnt lgkmcnt(0)
	v_mfma_f32_16x16x32_bf16 v[100:103], v[158:161], v[226:229], v[100:103]
	ds_read_b128 v[158:161], v20
	v_mfma_f32_16x16x32_bf16 v[108:111], v[166:169], v[162:165], v[108:111]
	v_mfma_f32_16x16x32_bf16 v[120:123], v[166:169], v[178:181], v[120:123]
	v_mfma_f32_16x16x32_bf16 v[132:135], v[166:169], v[222:225], v[132:135]
	s_mov_b32 m0, s35
	v_mfma_f32_16x16x32_bf16 v[140:143], v[166:169], v[226:229], v[140:143]
	global_load_lds_dwordx4 v4, s[46:47]
	ds_read_b128 v[166:169], v24
	v_mfma_f32_16x16x32_bf16 v[112:115], v[214:217], v[162:165], v[112:115]
	v_mfma_f32_16x16x32_bf16 v[52:55], v[218:221], v[162:165], v[52:55]
	ds_read_b128 v[162:165], v21
	v_mfma_f32_16x16x32_bf16 v[124:127], v[214:217], v[178:181], v[124:127]
	v_mfma_f32_16x16x32_bf16 v[68:71], v[218:221], v[178:181], v[68:71]
	ds_read_b128 v[178:181], v25
	s_mov_b32 m0, s36
	v_mfma_f32_16x16x32_bf16 v[136:139], v[214:217], v[222:225], v[136:139]
	global_load_lds_dwordx4 v4, s[48:49]
	v_mfma_f32_16x16x32_bf16 v[84:87], v[218:221], v[222:225], v[84:87]
	ds_read_b128 v[222:225], v26
	v_mfma_f32_16x16x32_bf16 v[150:153], v[214:217], v[226:229], v[150:153]
	ds_read_b128 v[214:217], v23
	v_mfma_f32_16x16x32_bf16 v[154:157], v[218:221], v[226:229], v[154:157]
	ds_read_b128 v[218:221], v22
	ds_read_b128 v[226:229], v27
	s_waitcnt lgkmcnt(6)
	v_mfma_f32_16x16x32_bf16 v[40:43], v[158:161], v[166:169], v[40:43]
	s_waitcnt lgkmcnt(5)
	s_mov_b32 m0, s37
	v_mfma_f32_16x16x32_bf16 v[44:47], v[162:165], v[166:169], v[44:47]
	global_load_lds_dwordx4 v146, s[46:47]
	s_waitcnt lgkmcnt(4)
	v_mfma_f32_16x16x32_bf16 v[56:59], v[158:161], v[178:181], v[56:59]
	v_mfma_f32_16x16x32_bf16 v[60:63], v[162:165], v[178:181], v[60:63]
	s_waitcnt lgkmcnt(3)
	v_mfma_f32_16x16x32_bf16 v[72:75], v[158:161], v[222:225], v[72:75]
	v_mfma_f32_16x16x32_bf16 v[76:79], v[162:165], v[222:225], v[76:79]
	s_waitcnt lgkmcnt(2)
	s_mov_b32 m0, s38
	v_mfma_f32_16x16x32_bf16 v[48:51], v[214:217], v[166:169], v[48:51]
	global_load_lds_dwordx4 v146, s[48:49]
	s_waitcnt lgkmcnt(1)
	v_mfma_f32_16x16x32_bf16 v[174:177], v[218:221], v[166:169], v[174:177]
	ds_read_b128 v[166:169], v28
	v_mfma_f32_16x16x32_bf16 v[64:67], v[214:217], v[178:181], v[64:67]
	v_mfma_f32_16x16x32_bf16 v[170:173], v[218:221], v[178:181], v[170:173]
	ds_read_b128 v[178:181], v29
	v_mfma_f32_16x16x32_bf16 v[80:83], v[214:217], v[222:225], v[80:83]
	v_mfma_f32_16x16x32_bf16 v[32:35], v[218:221], v[222:225], v[32:35]
	ds_read_b128 v[222:225], v30
	s_waitcnt lgkmcnt(3)
	v_mfma_f32_16x16x32_bf16 v[88:91], v[158:161], v[226:229], v[88:91]
	v_mfma_f32_16x16x32_bf16 v[92:95], v[162:165], v[226:229], v[92:95]
	v_mfma_f32_16x16x32_bf16 v[96:99], v[214:217], v[226:229], v[96:99]
	v_mfma_f32_16x16x32_bf16 v[36:39], v[218:221], v[226:229], v[36:39]
	ds_read_b128 v[226:229], v31
	s_waitcnt lgkmcnt(3)
	v_mfma_f32_16x16x32_bf16 v[104:107], v[158:161], v[166:169], v[104:107]
	v_mfma_f32_16x16x32_bf16 v[108:111], v[162:165], v[166:169], v[108:111]
	v_mfma_f32_16x16x32_bf16 v[112:115], v[214:217], v[166:169], v[112:115]
	v_mfma_f32_16x16x32_bf16 v[52:55], v[218:221], v[166:169], v[52:55]
	s_waitcnt lgkmcnt(2)
	v_mfma_f32_16x16x32_bf16 v[116:119], v[158:161], v[178:181], v[116:119]
	v_mfma_f32_16x16x32_bf16 v[120:123], v[162:165], v[178:181], v[120:123]
	v_mfma_f32_16x16x32_bf16 v[124:127], v[214:217], v[178:181], v[124:127]
	v_mfma_f32_16x16x32_bf16 v[68:71], v[218:221], v[178:181], v[68:71]
	s_waitcnt lgkmcnt(1)
	v_mfma_f32_16x16x32_bf16 v[128:131], v[158:161], v[222:225], v[128:131]
	v_mfma_f32_16x16x32_bf16 v[132:135], v[162:165], v[222:225], v[132:135]
	v_mfma_f32_16x16x32_bf16 v[136:139], v[214:217], v[222:225], v[136:139]
	v_mfma_f32_16x16x32_bf16 v[84:87], v[218:221], v[222:225], v[84:87]
	s_waitcnt lgkmcnt(0)
	v_mfma_f32_16x16x32_bf16 v[100:103], v[158:161], v[226:229], v[100:103]
	v_mfma_f32_16x16x32_bf16 v[140:143], v[162:165], v[226:229], v[140:143]
	v_mfma_f32_16x16x32_bf16 v[150:153], v[214:217], v[226:229], v[150:153]
	v_mfma_f32_16x16x32_bf16 v[154:157], v[218:221], v[226:229], v[154:157]
	s_add_u32 s46, s16, 0xc80
	s_addc_u32 s47, s17, 0
	s_add_u32 s48, s18, 0xc80
	s_waitcnt vmcnt(0)
	s_barrier
	s_addc_u32 s49, s19, 0
	ds_read_b128 v[158:161], v7 offset:32768
	ds_read_b128 v[162:165], v6
	ds_read_b128 v[166:169], v7 offset:34816
	ds_read_b128 v[178:181], v6 offset:2048
	ds_read_b128 v[214:217], v7 offset:36864
	ds_read_b128 v[218:221], v7 offset:38912
	ds_read_b128 v[222:225], v6 offset:4096
	ds_read_b128 v[226:229], v6 offset:6144
	s_waitcnt lgkmcnt(6)
	v_mfma_f32_16x16x32_bf16 v[40:43], v[158:161], v[162:165], v[40:43]
	s_waitcnt lgkmcnt(5)
	v_mfma_f32_16x16x32_bf16 v[44:47], v[166:169], v[162:165], v[44:47]
	s_waitcnt lgkmcnt(4)
	v_mfma_f32_16x16x32_bf16 v[56:59], v[158:161], v[178:181], v[56:59]
	s_mov_b32 m0, s25
	v_mfma_f32_16x16x32_bf16 v[60:63], v[166:169], v[178:181], v[60:63]
	global_load_lds_dwordx4 v0, s[46:47]
	s_waitcnt lgkmcnt(3)
	v_mfma_f32_16x16x32_bf16 v[48:51], v[214:217], v[162:165], v[48:51]
	v_mfma_f32_16x16x32_bf16 v[64:67], v[214:217], v[178:181], v[64:67]
	s_waitcnt lgkmcnt(2)
	v_mfma_f32_16x16x32_bf16 v[174:177], v[218:221], v[162:165], v[174:177]
	ds_read_b128 v[162:165], v6 offset:8192
	v_mfma_f32_16x16x32_bf16 v[170:173], v[218:221], v[178:181], v[170:173]
	ds_read_b128 v[178:181], v6 offset:10240
	s_waitcnt lgkmcnt(3)
	s_mov_b32 m0, s24
	v_mfma_f32_16x16x32_bf16 v[72:75], v[158:161], v[222:225], v[72:75]
	global_load_lds_dwordx4 v0, s[48:49]
	v_mfma_f32_16x16x32_bf16 v[76:79], v[166:169], v[222:225], v[76:79]
	v_mfma_f32_16x16x32_bf16 v[80:83], v[214:217], v[222:225], v[80:83]
	v_mfma_f32_16x16x32_bf16 v[32:35], v[218:221], v[222:225], v[32:35]
	ds_read_b128 v[222:225], v6 offset:12288
	s_waitcnt lgkmcnt(3)
	v_mfma_f32_16x16x32_bf16 v[88:91], v[158:161], v[226:229], v[88:91]
	s_mov_b32 m0, s39
	v_mfma_f32_16x16x32_bf16 v[92:95], v[166:169], v[226:229], v[92:95]
	global_load_lds_dwordx4 v2, s[46:47]
	v_mfma_f32_16x16x32_bf16 v[96:99], v[214:217], v[226:229], v[96:99]
	v_mfma_f32_16x16x32_bf16 v[36:39], v[218:221], v[226:229], v[36:39]
	ds_read_b128 v[226:229], v6 offset:14336
	s_waitcnt lgkmcnt(3)
	v_mfma_f32_16x16x32_bf16 v[104:107], v[158:161], v[162:165], v[104:107]
	s_waitcnt lgkmcnt(2)
	v_mfma_f32_16x16x32_bf16 v[116:119], v[158:161], v[178:181], v[116:119]
	s_waitcnt lgkmcnt(1)
	s_mov_b32 m0, s40
	v_mfma_f32_16x16x32_bf16 v[128:131], v[158:161], v[222:225], v[128:131]
	global_load_lds_dwordx4 v2, s[48:49]
	s_waitcnt lgkmcnt(0)
	v_mfma_f32_16x16x32_bf16 v[100:103], v[158:161], v[226:229], v[100:103]
	ds_read_b128 v[158:161], v7 offset:33792
	v_mfma_f32_16x16x32_bf16 v[108:111], v[166:169], v[162:165], v[108:111]
	v_mfma_f32_16x16x32_bf16 v[120:123], v[166:169], v[178:181], v[120:123]
	v_mfma_f32_16x16x32_bf16 v[132:135], v[166:169], v[222:225], v[132:135]
	s_mov_b32 m0, s41
	v_mfma_f32_16x16x32_bf16 v[140:143], v[166:169], v[226:229], v[140:143]
	global_load_lds_dwordx4 v4, s[46:47]
	ds_read_b128 v[166:169], v6 offset:1024
	v_mfma_f32_16x16x32_bf16 v[112:115], v[214:217], v[162:165], v[112:115]
	v_mfma_f32_16x16x32_bf16 v[52:55], v[218:221], v[162:165], v[52:55]
	ds_read_b128 v[162:165], v7 offset:35840
	v_mfma_f32_16x16x32_bf16 v[124:127], v[214:217], v[178:181], v[124:127]
	v_mfma_f32_16x16x32_bf16 v[68:71], v[218:221], v[178:181], v[68:71]
	ds_read_b128 v[178:181], v6 offset:3072
	s_mov_b32 m0, s42
	v_mfma_f32_16x16x32_bf16 v[136:139], v[214:217], v[222:225], v[136:139]
	global_load_lds_dwordx4 v4, s[48:49]
	v_mfma_f32_16x16x32_bf16 v[84:87], v[218:221], v[222:225], v[84:87]
	ds_read_b128 v[222:225], v6 offset:5120
	v_mfma_f32_16x16x32_bf16 v[150:153], v[214:217], v[226:229], v[150:153]
	ds_read_b128 v[214:217], v7 offset:37888
	v_mfma_f32_16x16x32_bf16 v[154:157], v[218:221], v[226:229], v[154:157]
	ds_read_b128 v[218:221], v7 offset:39936
	ds_read_b128 v[226:229], v6 offset:7168
	s_waitcnt lgkmcnt(6)
	v_mfma_f32_16x16x32_bf16 v[40:43], v[158:161], v[166:169], v[40:43]
	s_waitcnt lgkmcnt(5)
	s_mov_b32 m0, s43
	v_mfma_f32_16x16x32_bf16 v[44:47], v[162:165], v[166:169], v[44:47]
	global_load_lds_dwordx4 v146, s[46:47]
	s_waitcnt lgkmcnt(4)
	v_mfma_f32_16x16x32_bf16 v[56:59], v[158:161], v[178:181], v[56:59]
	v_mfma_f32_16x16x32_bf16 v[60:63], v[162:165], v[178:181], v[60:63]
	s_waitcnt lgkmcnt(3)
	v_mfma_f32_16x16x32_bf16 v[72:75], v[158:161], v[222:225], v[72:75]
	v_mfma_f32_16x16x32_bf16 v[76:79], v[162:165], v[222:225], v[76:79]
	s_waitcnt lgkmcnt(2)
	s_mov_b32 m0, s44
	v_mfma_f32_16x16x32_bf16 v[48:51], v[214:217], v[166:169], v[48:51]
	global_load_lds_dwordx4 v146, s[48:49]
	s_waitcnt lgkmcnt(1)
	v_mfma_f32_16x16x32_bf16 v[174:177], v[218:221], v[166:169], v[174:177]
	ds_read_b128 v[166:169], v6 offset:9216
	v_mfma_f32_16x16x32_bf16 v[64:67], v[214:217], v[178:181], v[64:67]
	v_mfma_f32_16x16x32_bf16 v[170:173], v[218:221], v[178:181], v[170:173]
	ds_read_b128 v[178:181], v6 offset:11264
	v_mfma_f32_16x16x32_bf16 v[80:83], v[214:217], v[222:225], v[80:83]
	v_mfma_f32_16x16x32_bf16 v[32:35], v[218:221], v[222:225], v[32:35]
	ds_read_b128 v[222:225], v6 offset:13312
	s_waitcnt lgkmcnt(3)
	v_mfma_f32_16x16x32_bf16 v[88:91], v[158:161], v[226:229], v[88:91]
	v_mfma_f32_16x16x32_bf16 v[92:95], v[162:165], v[226:229], v[92:95]
	v_mfma_f32_16x16x32_bf16 v[96:99], v[214:217], v[226:229], v[96:99]
	v_mfma_f32_16x16x32_bf16 v[36:39], v[218:221], v[226:229], v[36:39]
	ds_read_b128 v[226:229], v6 offset:15360
	s_waitcnt lgkmcnt(3)
	v_mfma_f32_16x16x32_bf16 v[104:107], v[158:161], v[166:169], v[104:107]
	v_mfma_f32_16x16x32_bf16 v[108:111], v[162:165], v[166:169], v[108:111]
	v_mfma_f32_16x16x32_bf16 v[112:115], v[214:217], v[166:169], v[112:115]
	v_mfma_f32_16x16x32_bf16 v[52:55], v[218:221], v[166:169], v[52:55]
	s_waitcnt lgkmcnt(2)
	v_mfma_f32_16x16x32_bf16 v[116:119], v[158:161], v[178:181], v[116:119]
	v_mfma_f32_16x16x32_bf16 v[120:123], v[162:165], v[178:181], v[120:123]
	v_mfma_f32_16x16x32_bf16 v[124:127], v[214:217], v[178:181], v[124:127]
	v_mfma_f32_16x16x32_bf16 v[68:71], v[218:221], v[178:181], v[68:71]
	s_waitcnt lgkmcnt(1)
	v_mfma_f32_16x16x32_bf16 v[128:131], v[158:161], v[222:225], v[128:131]
	v_mfma_f32_16x16x32_bf16 v[132:135], v[162:165], v[222:225], v[132:135]
	v_mfma_f32_16x16x32_bf16 v[136:139], v[214:217], v[222:225], v[136:139]
	v_mfma_f32_16x16x32_bf16 v[84:87], v[218:221], v[222:225], v[84:87]
	s_waitcnt lgkmcnt(0)
	v_mfma_f32_16x16x32_bf16 v[100:103], v[158:161], v[226:229], v[100:103]
	v_mfma_f32_16x16x32_bf16 v[140:143], v[162:165], v[226:229], v[140:143]
	v_mfma_f32_16x16x32_bf16 v[150:153], v[214:217], v[226:229], v[150:153]
	v_mfma_f32_16x16x32_bf16 v[154:157], v[218:221], v[226:229], v[154:157]
	s_add_u32 s46, s16, 0xd00
	s_addc_u32 s47, s17, 0
	s_add_u32 s48, s18, 0xd00
	s_waitcnt vmcnt(0)
	s_barrier
	s_addc_u32 s49, s19, 0
	ds_read_b128 v[158:161], v8
	ds_read_b128 v[162:165], v12
	ds_read_b128 v[166:169], v9
	ds_read_b128 v[178:181], v13
	ds_read_b128 v[214:217], v11
	ds_read_b128 v[218:221], v10
	ds_read_b128 v[222:225], v14
	ds_read_b128 v[226:229], v15
	s_waitcnt lgkmcnt(6)
	v_mfma_f32_16x16x32_bf16 v[40:43], v[158:161], v[162:165], v[40:43]
	s_waitcnt lgkmcnt(5)
	v_mfma_f32_16x16x32_bf16 v[44:47], v[166:169], v[162:165], v[44:47]
	s_waitcnt lgkmcnt(4)
	v_mfma_f32_16x16x32_bf16 v[56:59], v[158:161], v[178:181], v[56:59]
	s_mov_b32 m0, s1
	v_mfma_f32_16x16x32_bf16 v[60:63], v[166:169], v[178:181], v[60:63]
	global_load_lds_dwordx4 v0, s[46:47]
	s_waitcnt lgkmcnt(3)
	v_mfma_f32_16x16x32_bf16 v[48:51], v[214:217], v[162:165], v[48:51]
	v_mfma_f32_16x16x32_bf16 v[64:67], v[214:217], v[178:181], v[64:67]
	s_waitcnt lgkmcnt(2)
	v_mfma_f32_16x16x32_bf16 v[174:177], v[218:221], v[162:165], v[174:177]
	ds_read_b128 v[162:165], v16
	v_mfma_f32_16x16x32_bf16 v[170:173], v[218:221], v[178:181], v[170:173]
	ds_read_b128 v[178:181], v17
	s_waitcnt lgkmcnt(3)
	s_mov_b32 m0, s30
	v_mfma_f32_16x16x32_bf16 v[72:75], v[158:161], v[222:225], v[72:75]
	global_load_lds_dwordx4 v0, s[48:49]
	v_mfma_f32_16x16x32_bf16 v[76:79], v[166:169], v[222:225], v[76:79]
	v_mfma_f32_16x16x32_bf16 v[80:83], v[214:217], v[222:225], v[80:83]
	v_mfma_f32_16x16x32_bf16 v[32:35], v[218:221], v[222:225], v[32:35]
	ds_read_b128 v[222:225], v18
	s_waitcnt lgkmcnt(3)
	v_mfma_f32_16x16x32_bf16 v[88:91], v[158:161], v[226:229], v[88:91]
	s_mov_b32 m0, s31
	v_mfma_f32_16x16x32_bf16 v[92:95], v[166:169], v[226:229], v[92:95]
	global_load_lds_dwordx4 v2, s[46:47]
	v_mfma_f32_16x16x32_bf16 v[96:99], v[214:217], v[226:229], v[96:99]
	v_mfma_f32_16x16x32_bf16 v[36:39], v[218:221], v[226:229], v[36:39]
	ds_read_b128 v[226:229], v19
	s_waitcnt lgkmcnt(3)
	v_mfma_f32_16x16x32_bf16 v[104:107], v[158:161], v[162:165], v[104:107]
	s_waitcnt lgkmcnt(2)
	v_mfma_f32_16x16x32_bf16 v[116:119], v[158:161], v[178:181], v[116:119]
	s_waitcnt lgkmcnt(1)
	s_mov_b32 m0, s34
	v_mfma_f32_16x16x32_bf16 v[128:131], v[158:161], v[222:225], v[128:131]
	global_load_lds_dwordx4 v2, s[48:49]
	s_waitcnt lgkmcnt(0)
	v_mfma_f32_16x16x32_bf16 v[100:103], v[158:161], v[226:229], v[100:103]
	ds_read_b128 v[158:161], v20
	v_mfma_f32_16x16x32_bf16 v[108:111], v[166:169], v[162:165], v[108:111]
	v_mfma_f32_16x16x32_bf16 v[120:123], v[166:169], v[178:181], v[120:123]
	v_mfma_f32_16x16x32_bf16 v[132:135], v[166:169], v[222:225], v[132:135]
	s_mov_b32 m0, s35
	v_mfma_f32_16x16x32_bf16 v[140:143], v[166:169], v[226:229], v[140:143]
	global_load_lds_dwordx4 v4, s[46:47]
	ds_read_b128 v[166:169], v24
	v_mfma_f32_16x16x32_bf16 v[112:115], v[214:217], v[162:165], v[112:115]
	v_mfma_f32_16x16x32_bf16 v[52:55], v[218:221], v[162:165], v[52:55]
	ds_read_b128 v[162:165], v21
	v_mfma_f32_16x16x32_bf16 v[124:127], v[214:217], v[178:181], v[124:127]
	v_mfma_f32_16x16x32_bf16 v[68:71], v[218:221], v[178:181], v[68:71]
	ds_read_b128 v[178:181], v25
	s_mov_b32 m0, s36
	v_mfma_f32_16x16x32_bf16 v[136:139], v[214:217], v[222:225], v[136:139]
	global_load_lds_dwordx4 v4, s[48:49]
	v_mfma_f32_16x16x32_bf16 v[84:87], v[218:221], v[222:225], v[84:87]
	ds_read_b128 v[222:225], v26
	v_mfma_f32_16x16x32_bf16 v[150:153], v[214:217], v[226:229], v[150:153]
	ds_read_b128 v[214:217], v23
	v_mfma_f32_16x16x32_bf16 v[154:157], v[218:221], v[226:229], v[154:157]
	ds_read_b128 v[218:221], v22
	ds_read_b128 v[226:229], v27
	s_waitcnt lgkmcnt(6)
	v_mfma_f32_16x16x32_bf16 v[40:43], v[158:161], v[166:169], v[40:43]
	s_waitcnt lgkmcnt(5)
	s_mov_b32 m0, s37
	v_mfma_f32_16x16x32_bf16 v[44:47], v[162:165], v[166:169], v[44:47]
	global_load_lds_dwordx4 v146, s[46:47]
	s_waitcnt lgkmcnt(4)
	v_mfma_f32_16x16x32_bf16 v[56:59], v[158:161], v[178:181], v[56:59]
	v_mfma_f32_16x16x32_bf16 v[60:63], v[162:165], v[178:181], v[60:63]
	s_waitcnt lgkmcnt(3)
	v_mfma_f32_16x16x32_bf16 v[72:75], v[158:161], v[222:225], v[72:75]
	v_mfma_f32_16x16x32_bf16 v[76:79], v[162:165], v[222:225], v[76:79]
	s_waitcnt lgkmcnt(2)
	s_mov_b32 m0, s38
	v_mfma_f32_16x16x32_bf16 v[48:51], v[214:217], v[166:169], v[48:51]
	global_load_lds_dwordx4 v146, s[48:49]
	s_waitcnt lgkmcnt(1)
	v_mfma_f32_16x16x32_bf16 v[174:177], v[218:221], v[166:169], v[174:177]
	ds_read_b128 v[166:169], v28
	v_mfma_f32_16x16x32_bf16 v[64:67], v[214:217], v[178:181], v[64:67]
	v_mfma_f32_16x16x32_bf16 v[170:173], v[218:221], v[178:181], v[170:173]
	ds_read_b128 v[178:181], v29
	v_mfma_f32_16x16x32_bf16 v[80:83], v[214:217], v[222:225], v[80:83]
	v_mfma_f32_16x16x32_bf16 v[32:35], v[218:221], v[222:225], v[32:35]
	ds_read_b128 v[222:225], v30
	s_waitcnt lgkmcnt(3)
	v_mfma_f32_16x16x32_bf16 v[88:91], v[158:161], v[226:229], v[88:91]
	v_mfma_f32_16x16x32_bf16 v[92:95], v[162:165], v[226:229], v[92:95]
	v_mfma_f32_16x16x32_bf16 v[96:99], v[214:217], v[226:229], v[96:99]
	v_mfma_f32_16x16x32_bf16 v[36:39], v[218:221], v[226:229], v[36:39]
	ds_read_b128 v[226:229], v31
	s_waitcnt lgkmcnt(3)
	v_mfma_f32_16x16x32_bf16 v[104:107], v[158:161], v[166:169], v[104:107]
	v_mfma_f32_16x16x32_bf16 v[108:111], v[162:165], v[166:169], v[108:111]
	v_mfma_f32_16x16x32_bf16 v[112:115], v[214:217], v[166:169], v[112:115]
	v_mfma_f32_16x16x32_bf16 v[52:55], v[218:221], v[166:169], v[52:55]
	s_waitcnt lgkmcnt(2)
	v_mfma_f32_16x16x32_bf16 v[116:119], v[158:161], v[178:181], v[116:119]
	v_mfma_f32_16x16x32_bf16 v[120:123], v[162:165], v[178:181], v[120:123]
	v_mfma_f32_16x16x32_bf16 v[124:127], v[214:217], v[178:181], v[124:127]
	v_mfma_f32_16x16x32_bf16 v[68:71], v[218:221], v[178:181], v[68:71]
	s_waitcnt lgkmcnt(1)
	v_mfma_f32_16x16x32_bf16 v[128:131], v[158:161], v[222:225], v[128:131]
	v_mfma_f32_16x16x32_bf16 v[132:135], v[162:165], v[222:225], v[132:135]
	v_mfma_f32_16x16x32_bf16 v[136:139], v[214:217], v[222:225], v[136:139]
	v_mfma_f32_16x16x32_bf16 v[84:87], v[218:221], v[222:225], v[84:87]
	s_waitcnt lgkmcnt(0)
	v_mfma_f32_16x16x32_bf16 v[100:103], v[158:161], v[226:229], v[100:103]
	v_mfma_f32_16x16x32_bf16 v[140:143], v[162:165], v[226:229], v[140:143]
	v_mfma_f32_16x16x32_bf16 v[150:153], v[214:217], v[226:229], v[150:153]
	v_mfma_f32_16x16x32_bf16 v[154:157], v[218:221], v[226:229], v[154:157]
	s_add_u32 s46, s16, 0xd80
	s_addc_u32 s47, s17, 0
	s_add_u32 s48, s18, 0xd80
	s_waitcnt vmcnt(0)
	s_barrier
	s_addc_u32 s49, s19, 0
	ds_read_b128 v[158:161], v7 offset:32768
	ds_read_b128 v[162:165], v6
	ds_read_b128 v[166:169], v7 offset:34816
	ds_read_b128 v[178:181], v6 offset:2048
	ds_read_b128 v[214:217], v7 offset:36864
	ds_read_b128 v[218:221], v7 offset:38912
	ds_read_b128 v[222:225], v6 offset:4096
	ds_read_b128 v[226:229], v6 offset:6144
	s_waitcnt lgkmcnt(6)
	v_mfma_f32_16x16x32_bf16 v[40:43], v[158:161], v[162:165], v[40:43]
	s_waitcnt lgkmcnt(5)
	v_mfma_f32_16x16x32_bf16 v[44:47], v[166:169], v[162:165], v[44:47]
	s_waitcnt lgkmcnt(4)
	v_mfma_f32_16x16x32_bf16 v[56:59], v[158:161], v[178:181], v[56:59]
	s_mov_b32 m0, s25
	v_mfma_f32_16x16x32_bf16 v[60:63], v[166:169], v[178:181], v[60:63]
	global_load_lds_dwordx4 v0, s[46:47]
	s_waitcnt lgkmcnt(3)
	v_mfma_f32_16x16x32_bf16 v[48:51], v[214:217], v[162:165], v[48:51]
	v_mfma_f32_16x16x32_bf16 v[64:67], v[214:217], v[178:181], v[64:67]
	s_waitcnt lgkmcnt(2)
	v_mfma_f32_16x16x32_bf16 v[174:177], v[218:221], v[162:165], v[174:177]
	ds_read_b128 v[162:165], v6 offset:8192
	v_mfma_f32_16x16x32_bf16 v[170:173], v[218:221], v[178:181], v[170:173]
	ds_read_b128 v[178:181], v6 offset:10240
	s_waitcnt lgkmcnt(3)
	s_mov_b32 m0, s24
	v_mfma_f32_16x16x32_bf16 v[72:75], v[158:161], v[222:225], v[72:75]
	global_load_lds_dwordx4 v0, s[48:49]
	v_mfma_f32_16x16x32_bf16 v[76:79], v[166:169], v[222:225], v[76:79]
	v_mfma_f32_16x16x32_bf16 v[80:83], v[214:217], v[222:225], v[80:83]
	v_mfma_f32_16x16x32_bf16 v[32:35], v[218:221], v[222:225], v[32:35]
	ds_read_b128 v[222:225], v6 offset:12288
	s_waitcnt lgkmcnt(3)
	v_mfma_f32_16x16x32_bf16 v[88:91], v[158:161], v[226:229], v[88:91]
	s_mov_b32 m0, s39
	v_mfma_f32_16x16x32_bf16 v[92:95], v[166:169], v[226:229], v[92:95]
	global_load_lds_dwordx4 v2, s[46:47]
	v_mfma_f32_16x16x32_bf16 v[96:99], v[214:217], v[226:229], v[96:99]
	v_mfma_f32_16x16x32_bf16 v[36:39], v[218:221], v[226:229], v[36:39]
	ds_read_b128 v[226:229], v6 offset:14336
	s_waitcnt lgkmcnt(3)
	v_mfma_f32_16x16x32_bf16 v[104:107], v[158:161], v[162:165], v[104:107]
	s_waitcnt lgkmcnt(2)
	v_mfma_f32_16x16x32_bf16 v[116:119], v[158:161], v[178:181], v[116:119]
	s_waitcnt lgkmcnt(1)
	s_mov_b32 m0, s40
	v_mfma_f32_16x16x32_bf16 v[128:131], v[158:161], v[222:225], v[128:131]
	global_load_lds_dwordx4 v2, s[48:49]
	s_waitcnt lgkmcnt(0)
	v_mfma_f32_16x16x32_bf16 v[100:103], v[158:161], v[226:229], v[100:103]
	ds_read_b128 v[158:161], v7 offset:33792
	v_mfma_f32_16x16x32_bf16 v[108:111], v[166:169], v[162:165], v[108:111]
	v_mfma_f32_16x16x32_bf16 v[120:123], v[166:169], v[178:181], v[120:123]
	v_mfma_f32_16x16x32_bf16 v[132:135], v[166:169], v[222:225], v[132:135]
	s_mov_b32 m0, s41
	v_mfma_f32_16x16x32_bf16 v[140:143], v[166:169], v[226:229], v[140:143]
	global_load_lds_dwordx4 v4, s[46:47]
	ds_read_b128 v[166:169], v6 offset:1024
	v_mfma_f32_16x16x32_bf16 v[112:115], v[214:217], v[162:165], v[112:115]
	v_mfma_f32_16x16x32_bf16 v[52:55], v[218:221], v[162:165], v[52:55]
	ds_read_b128 v[162:165], v7 offset:35840
	v_mfma_f32_16x16x32_bf16 v[124:127], v[214:217], v[178:181], v[124:127]
	v_mfma_f32_16x16x32_bf16 v[68:71], v[218:221], v[178:181], v[68:71]
	ds_read_b128 v[178:181], v6 offset:3072
	s_mov_b32 m0, s42
	v_mfma_f32_16x16x32_bf16 v[136:139], v[214:217], v[222:225], v[136:139]
	global_load_lds_dwordx4 v4, s[48:49]
	v_mfma_f32_16x16x32_bf16 v[84:87], v[218:221], v[222:225], v[84:87]
	ds_read_b128 v[222:225], v6 offset:5120
	v_mfma_f32_16x16x32_bf16 v[150:153], v[214:217], v[226:229], v[150:153]
	ds_read_b128 v[214:217], v7 offset:37888
	v_mfma_f32_16x16x32_bf16 v[154:157], v[218:221], v[226:229], v[154:157]
	ds_read_b128 v[218:221], v7 offset:39936
	ds_read_b128 v[226:229], v6 offset:7168
	s_waitcnt lgkmcnt(6)
	v_mfma_f32_16x16x32_bf16 v[40:43], v[158:161], v[166:169], v[40:43]
	s_waitcnt lgkmcnt(5)
	s_mov_b32 m0, s43
	v_mfma_f32_16x16x32_bf16 v[44:47], v[162:165], v[166:169], v[44:47]
	global_load_lds_dwordx4 v146, s[46:47]
	s_waitcnt lgkmcnt(4)
	v_mfma_f32_16x16x32_bf16 v[56:59], v[158:161], v[178:181], v[56:59]
	v_mfma_f32_16x16x32_bf16 v[60:63], v[162:165], v[178:181], v[60:63]
	s_waitcnt lgkmcnt(3)
	v_mfma_f32_16x16x32_bf16 v[72:75], v[158:161], v[222:225], v[72:75]
	v_mfma_f32_16x16x32_bf16 v[76:79], v[162:165], v[222:225], v[76:79]
	s_waitcnt lgkmcnt(2)
	s_mov_b32 m0, s44
	v_mfma_f32_16x16x32_bf16 v[48:51], v[214:217], v[166:169], v[48:51]
	global_load_lds_dwordx4 v146, s[48:49]
	s_waitcnt lgkmcnt(1)
	v_mfma_f32_16x16x32_bf16 v[174:177], v[218:221], v[166:169], v[174:177]
	ds_read_b128 v[166:169], v6 offset:9216
	v_mfma_f32_16x16x32_bf16 v[64:67], v[214:217], v[178:181], v[64:67]
	v_mfma_f32_16x16x32_bf16 v[170:173], v[218:221], v[178:181], v[170:173]
	ds_read_b128 v[178:181], v6 offset:11264
	v_mfma_f32_16x16x32_bf16 v[80:83], v[214:217], v[222:225], v[80:83]
	v_mfma_f32_16x16x32_bf16 v[32:35], v[218:221], v[222:225], v[32:35]
	ds_read_b128 v[222:225], v6 offset:13312
	s_waitcnt lgkmcnt(3)
	v_mfma_f32_16x16x32_bf16 v[88:91], v[158:161], v[226:229], v[88:91]
	v_mfma_f32_16x16x32_bf16 v[92:95], v[162:165], v[226:229], v[92:95]
	v_mfma_f32_16x16x32_bf16 v[96:99], v[214:217], v[226:229], v[96:99]
	v_mfma_f32_16x16x32_bf16 v[36:39], v[218:221], v[226:229], v[36:39]
	ds_read_b128 v[226:229], v6 offset:15360
	s_waitcnt lgkmcnt(3)
	v_mfma_f32_16x16x32_bf16 v[104:107], v[158:161], v[166:169], v[104:107]
	v_mfma_f32_16x16x32_bf16 v[108:111], v[162:165], v[166:169], v[108:111]
	v_mfma_f32_16x16x32_bf16 v[112:115], v[214:217], v[166:169], v[112:115]
	v_mfma_f32_16x16x32_bf16 v[52:55], v[218:221], v[166:169], v[52:55]
	s_waitcnt lgkmcnt(2)
	v_mfma_f32_16x16x32_bf16 v[116:119], v[158:161], v[178:181], v[116:119]
	v_mfma_f32_16x16x32_bf16 v[120:123], v[162:165], v[178:181], v[120:123]
	v_mfma_f32_16x16x32_bf16 v[124:127], v[214:217], v[178:181], v[124:127]
	v_mfma_f32_16x16x32_bf16 v[68:71], v[218:221], v[178:181], v[68:71]
	s_waitcnt lgkmcnt(1)
	v_mfma_f32_16x16x32_bf16 v[128:131], v[158:161], v[222:225], v[128:131]
	v_mfma_f32_16x16x32_bf16 v[132:135], v[162:165], v[222:225], v[132:135]
	v_mfma_f32_16x16x32_bf16 v[136:139], v[214:217], v[222:225], v[136:139]
	v_mfma_f32_16x16x32_bf16 v[84:87], v[218:221], v[222:225], v[84:87]
	s_waitcnt lgkmcnt(0)
	v_mfma_f32_16x16x32_bf16 v[100:103], v[158:161], v[226:229], v[100:103]
	v_mfma_f32_16x16x32_bf16 v[140:143], v[162:165], v[226:229], v[140:143]
	v_mfma_f32_16x16x32_bf16 v[150:153], v[214:217], v[226:229], v[150:153]
	v_mfma_f32_16x16x32_bf16 v[154:157], v[218:221], v[226:229], v[154:157]
	s_add_u32 s46, s16, 0xe00
	s_addc_u32 s47, s17, 0
	s_add_u32 s48, s18, 0xe00
	s_waitcnt vmcnt(0)
	s_barrier
	s_addc_u32 s49, s19, 0
	ds_read_b128 v[158:161], v8
	ds_read_b128 v[162:165], v12
	ds_read_b128 v[166:169], v9
	ds_read_b128 v[178:181], v13
	ds_read_b128 v[214:217], v11
	ds_read_b128 v[218:221], v10
	ds_read_b128 v[222:225], v14
	ds_read_b128 v[226:229], v15
	s_waitcnt lgkmcnt(6)
	v_mfma_f32_16x16x32_bf16 v[40:43], v[158:161], v[162:165], v[40:43]
	s_waitcnt lgkmcnt(5)
	v_mfma_f32_16x16x32_bf16 v[44:47], v[166:169], v[162:165], v[44:47]
	s_waitcnt lgkmcnt(4)
	v_mfma_f32_16x16x32_bf16 v[56:59], v[158:161], v[178:181], v[56:59]
	s_mov_b32 m0, s1
	v_mfma_f32_16x16x32_bf16 v[60:63], v[166:169], v[178:181], v[60:63]
	global_load_lds_dwordx4 v0, s[46:47]
	s_waitcnt lgkmcnt(3)
	v_mfma_f32_16x16x32_bf16 v[48:51], v[214:217], v[162:165], v[48:51]
	v_mfma_f32_16x16x32_bf16 v[64:67], v[214:217], v[178:181], v[64:67]
	s_waitcnt lgkmcnt(2)
	v_mfma_f32_16x16x32_bf16 v[174:177], v[218:221], v[162:165], v[174:177]
	ds_read_b128 v[162:165], v16
	v_mfma_f32_16x16x32_bf16 v[170:173], v[218:221], v[178:181], v[170:173]
	ds_read_b128 v[178:181], v17
	s_waitcnt lgkmcnt(3)
	s_mov_b32 m0, s30
	v_mfma_f32_16x16x32_bf16 v[72:75], v[158:161], v[222:225], v[72:75]
	global_load_lds_dwordx4 v0, s[48:49]
	v_mfma_f32_16x16x32_bf16 v[76:79], v[166:169], v[222:225], v[76:79]
	v_mfma_f32_16x16x32_bf16 v[80:83], v[214:217], v[222:225], v[80:83]
	v_mfma_f32_16x16x32_bf16 v[32:35], v[218:221], v[222:225], v[32:35]
	ds_read_b128 v[222:225], v18
	s_waitcnt lgkmcnt(3)
	v_mfma_f32_16x16x32_bf16 v[88:91], v[158:161], v[226:229], v[88:91]
	s_mov_b32 m0, s31
	v_mfma_f32_16x16x32_bf16 v[92:95], v[166:169], v[226:229], v[92:95]
	global_load_lds_dwordx4 v2, s[46:47]
	v_mfma_f32_16x16x32_bf16 v[96:99], v[214:217], v[226:229], v[96:99]
	v_mfma_f32_16x16x32_bf16 v[36:39], v[218:221], v[226:229], v[36:39]
	ds_read_b128 v[226:229], v19
	s_waitcnt lgkmcnt(3)
	v_mfma_f32_16x16x32_bf16 v[104:107], v[158:161], v[162:165], v[104:107]
	s_waitcnt lgkmcnt(2)
	v_mfma_f32_16x16x32_bf16 v[116:119], v[158:161], v[178:181], v[116:119]
	s_waitcnt lgkmcnt(1)
	s_mov_b32 m0, s34
	v_mfma_f32_16x16x32_bf16 v[128:131], v[158:161], v[222:225], v[128:131]
	global_load_lds_dwordx4 v2, s[48:49]
	s_waitcnt lgkmcnt(0)
	v_mfma_f32_16x16x32_bf16 v[100:103], v[158:161], v[226:229], v[100:103]
	ds_read_b128 v[158:161], v20
	v_mfma_f32_16x16x32_bf16 v[108:111], v[166:169], v[162:165], v[108:111]
	v_mfma_f32_16x16x32_bf16 v[120:123], v[166:169], v[178:181], v[120:123]
	v_mfma_f32_16x16x32_bf16 v[132:135], v[166:169], v[222:225], v[132:135]
	s_mov_b32 m0, s35
	v_mfma_f32_16x16x32_bf16 v[140:143], v[166:169], v[226:229], v[140:143]
	global_load_lds_dwordx4 v4, s[46:47]
	ds_read_b128 v[166:169], v24
	v_mfma_f32_16x16x32_bf16 v[112:115], v[214:217], v[162:165], v[112:115]
	v_mfma_f32_16x16x32_bf16 v[52:55], v[218:221], v[162:165], v[52:55]
	ds_read_b128 v[162:165], v21
	v_mfma_f32_16x16x32_bf16 v[124:127], v[214:217], v[178:181], v[124:127]
	v_mfma_f32_16x16x32_bf16 v[68:71], v[218:221], v[178:181], v[68:71]
	ds_read_b128 v[178:181], v25
	s_mov_b32 m0, s36
	v_mfma_f32_16x16x32_bf16 v[136:139], v[214:217], v[222:225], v[136:139]
	global_load_lds_dwordx4 v4, s[48:49]
	v_mfma_f32_16x16x32_bf16 v[84:87], v[218:221], v[222:225], v[84:87]
	ds_read_b128 v[222:225], v26
	v_mfma_f32_16x16x32_bf16 v[150:153], v[214:217], v[226:229], v[150:153]
	ds_read_b128 v[214:217], v23
	v_mfma_f32_16x16x32_bf16 v[154:157], v[218:221], v[226:229], v[154:157]
	ds_read_b128 v[218:221], v22
	ds_read_b128 v[226:229], v27
	s_waitcnt lgkmcnt(6)
	v_mfma_f32_16x16x32_bf16 v[40:43], v[158:161], v[166:169], v[40:43]
	s_waitcnt lgkmcnt(5)
	s_mov_b32 m0, s37
	v_mfma_f32_16x16x32_bf16 v[44:47], v[162:165], v[166:169], v[44:47]
	global_load_lds_dwordx4 v146, s[46:47]
	s_waitcnt lgkmcnt(4)
	v_mfma_f32_16x16x32_bf16 v[56:59], v[158:161], v[178:181], v[56:59]
	v_mfma_f32_16x16x32_bf16 v[60:63], v[162:165], v[178:181], v[60:63]
	s_waitcnt lgkmcnt(3)
	v_mfma_f32_16x16x32_bf16 v[72:75], v[158:161], v[222:225], v[72:75]
	v_mfma_f32_16x16x32_bf16 v[76:79], v[162:165], v[222:225], v[76:79]
	s_waitcnt lgkmcnt(2)
	s_mov_b32 m0, s38
	v_mfma_f32_16x16x32_bf16 v[48:51], v[214:217], v[166:169], v[48:51]
	global_load_lds_dwordx4 v146, s[48:49]
	s_waitcnt lgkmcnt(1)
	v_mfma_f32_16x16x32_bf16 v[174:177], v[218:221], v[166:169], v[174:177]
	ds_read_b128 v[166:169], v28
	v_mfma_f32_16x16x32_bf16 v[64:67], v[214:217], v[178:181], v[64:67]
	v_mfma_f32_16x16x32_bf16 v[170:173], v[218:221], v[178:181], v[170:173]
	ds_read_b128 v[178:181], v29
	v_mfma_f32_16x16x32_bf16 v[80:83], v[214:217], v[222:225], v[80:83]
	v_mfma_f32_16x16x32_bf16 v[32:35], v[218:221], v[222:225], v[32:35]
	ds_read_b128 v[222:225], v30
	s_waitcnt lgkmcnt(3)
	v_mfma_f32_16x16x32_bf16 v[88:91], v[158:161], v[226:229], v[88:91]
	v_mfma_f32_16x16x32_bf16 v[92:95], v[162:165], v[226:229], v[92:95]
	v_mfma_f32_16x16x32_bf16 v[96:99], v[214:217], v[226:229], v[96:99]
	v_mfma_f32_16x16x32_bf16 v[36:39], v[218:221], v[226:229], v[36:39]
	ds_read_b128 v[226:229], v31
	s_waitcnt lgkmcnt(3)
	v_mfma_f32_16x16x32_bf16 v[104:107], v[158:161], v[166:169], v[104:107]
	v_mfma_f32_16x16x32_bf16 v[108:111], v[162:165], v[166:169], v[108:111]
	v_mfma_f32_16x16x32_bf16 v[112:115], v[214:217], v[166:169], v[112:115]
	v_mfma_f32_16x16x32_bf16 v[52:55], v[218:221], v[166:169], v[52:55]
	s_waitcnt lgkmcnt(2)
	v_mfma_f32_16x16x32_bf16 v[116:119], v[158:161], v[178:181], v[116:119]
	v_mfma_f32_16x16x32_bf16 v[120:123], v[162:165], v[178:181], v[120:123]
	v_mfma_f32_16x16x32_bf16 v[124:127], v[214:217], v[178:181], v[124:127]
	v_mfma_f32_16x16x32_bf16 v[68:71], v[218:221], v[178:181], v[68:71]
	s_waitcnt lgkmcnt(1)
	v_mfma_f32_16x16x32_bf16 v[128:131], v[158:161], v[222:225], v[128:131]
	v_mfma_f32_16x16x32_bf16 v[132:135], v[162:165], v[222:225], v[132:135]
	v_mfma_f32_16x16x32_bf16 v[136:139], v[214:217], v[222:225], v[136:139]
	v_mfma_f32_16x16x32_bf16 v[84:87], v[218:221], v[222:225], v[84:87]
	s_waitcnt lgkmcnt(0)
	v_mfma_f32_16x16x32_bf16 v[100:103], v[158:161], v[226:229], v[100:103]
	v_mfma_f32_16x16x32_bf16 v[140:143], v[162:165], v[226:229], v[140:143]
	v_mfma_f32_16x16x32_bf16 v[150:153], v[214:217], v[226:229], v[150:153]
	v_mfma_f32_16x16x32_bf16 v[154:157], v[218:221], v[226:229], v[154:157]
	s_add_u32 s46, s16, 0xe80
	s_addc_u32 s47, s17, 0
	s_add_u32 s48, s18, 0xe80
	s_waitcnt vmcnt(0)
	s_barrier
	s_addc_u32 s49, s19, 0
	ds_read_b128 v[158:161], v7 offset:32768
	ds_read_b128 v[162:165], v6
	ds_read_b128 v[166:169], v7 offset:34816
	ds_read_b128 v[178:181], v6 offset:2048
	ds_read_b128 v[214:217], v7 offset:36864
	ds_read_b128 v[218:221], v7 offset:38912
	ds_read_b128 v[222:225], v6 offset:4096
	ds_read_b128 v[226:229], v6 offset:6144
	s_waitcnt lgkmcnt(6)
	v_mfma_f32_16x16x32_bf16 v[40:43], v[158:161], v[162:165], v[40:43]
	s_waitcnt lgkmcnt(5)
	v_mfma_f32_16x16x32_bf16 v[44:47], v[166:169], v[162:165], v[44:47]
	s_waitcnt lgkmcnt(4)
	v_mfma_f32_16x16x32_bf16 v[56:59], v[158:161], v[178:181], v[56:59]
	s_mov_b32 m0, s25
	v_mfma_f32_16x16x32_bf16 v[60:63], v[166:169], v[178:181], v[60:63]
	global_load_lds_dwordx4 v0, s[46:47]
	s_waitcnt lgkmcnt(3)
	v_mfma_f32_16x16x32_bf16 v[48:51], v[214:217], v[162:165], v[48:51]
	v_mfma_f32_16x16x32_bf16 v[64:67], v[214:217], v[178:181], v[64:67]
	s_waitcnt lgkmcnt(2)
	v_mfma_f32_16x16x32_bf16 v[174:177], v[218:221], v[162:165], v[174:177]
	ds_read_b128 v[162:165], v6 offset:8192
	v_mfma_f32_16x16x32_bf16 v[170:173], v[218:221], v[178:181], v[170:173]
	ds_read_b128 v[178:181], v6 offset:10240
	s_waitcnt lgkmcnt(3)
	s_mov_b32 m0, s24
	v_mfma_f32_16x16x32_bf16 v[72:75], v[158:161], v[222:225], v[72:75]
	global_load_lds_dwordx4 v0, s[48:49]
	v_mfma_f32_16x16x32_bf16 v[76:79], v[166:169], v[222:225], v[76:79]
	v_mfma_f32_16x16x32_bf16 v[80:83], v[214:217], v[222:225], v[80:83]
	v_mfma_f32_16x16x32_bf16 v[32:35], v[218:221], v[222:225], v[32:35]
	ds_read_b128 v[222:225], v6 offset:12288
	s_waitcnt lgkmcnt(3)
	v_mfma_f32_16x16x32_bf16 v[88:91], v[158:161], v[226:229], v[88:91]
	s_mov_b32 m0, s39
	v_mfma_f32_16x16x32_bf16 v[92:95], v[166:169], v[226:229], v[92:95]
	global_load_lds_dwordx4 v2, s[46:47]
	v_mfma_f32_16x16x32_bf16 v[96:99], v[214:217], v[226:229], v[96:99]
	v_mfma_f32_16x16x32_bf16 v[36:39], v[218:221], v[226:229], v[36:39]
	ds_read_b128 v[226:229], v6 offset:14336
	s_waitcnt lgkmcnt(3)
	v_mfma_f32_16x16x32_bf16 v[104:107], v[158:161], v[162:165], v[104:107]
	s_waitcnt lgkmcnt(2)
	v_mfma_f32_16x16x32_bf16 v[116:119], v[158:161], v[178:181], v[116:119]
	s_waitcnt lgkmcnt(1)
	s_mov_b32 m0, s40
	v_mfma_f32_16x16x32_bf16 v[128:131], v[158:161], v[222:225], v[128:131]
	global_load_lds_dwordx4 v2, s[48:49]
	s_waitcnt lgkmcnt(0)
	v_mfma_f32_16x16x32_bf16 v[100:103], v[158:161], v[226:229], v[100:103]
	ds_read_b128 v[158:161], v7 offset:33792
	v_mfma_f32_16x16x32_bf16 v[108:111], v[166:169], v[162:165], v[108:111]
	v_mfma_f32_16x16x32_bf16 v[120:123], v[166:169], v[178:181], v[120:123]
	v_mfma_f32_16x16x32_bf16 v[132:135], v[166:169], v[222:225], v[132:135]
	s_mov_b32 m0, s41
	v_mfma_f32_16x16x32_bf16 v[140:143], v[166:169], v[226:229], v[140:143]
	global_load_lds_dwordx4 v4, s[46:47]
	ds_read_b128 v[166:169], v6 offset:1024
	v_mfma_f32_16x16x32_bf16 v[112:115], v[214:217], v[162:165], v[112:115]
	v_mfma_f32_16x16x32_bf16 v[52:55], v[218:221], v[162:165], v[52:55]
	ds_read_b128 v[162:165], v7 offset:35840
	v_mfma_f32_16x16x32_bf16 v[124:127], v[214:217], v[178:181], v[124:127]
	v_mfma_f32_16x16x32_bf16 v[68:71], v[218:221], v[178:181], v[68:71]
	ds_read_b128 v[178:181], v6 offset:3072
	s_mov_b32 m0, s42
	v_mfma_f32_16x16x32_bf16 v[136:139], v[214:217], v[222:225], v[136:139]
	global_load_lds_dwordx4 v4, s[48:49]
	v_mfma_f32_16x16x32_bf16 v[84:87], v[218:221], v[222:225], v[84:87]
	ds_read_b128 v[222:225], v6 offset:5120
	v_mfma_f32_16x16x32_bf16 v[150:153], v[214:217], v[226:229], v[150:153]
	ds_read_b128 v[214:217], v7 offset:37888
	v_mfma_f32_16x16x32_bf16 v[154:157], v[218:221], v[226:229], v[154:157]
	ds_read_b128 v[218:221], v7 offset:39936
	ds_read_b128 v[226:229], v6 offset:7168
	s_waitcnt lgkmcnt(6)
	v_mfma_f32_16x16x32_bf16 v[40:43], v[158:161], v[166:169], v[40:43]
	s_waitcnt lgkmcnt(5)
	s_mov_b32 m0, s43
	v_mfma_f32_16x16x32_bf16 v[44:47], v[162:165], v[166:169], v[44:47]
	global_load_lds_dwordx4 v146, s[46:47]
	s_waitcnt lgkmcnt(4)
	v_mfma_f32_16x16x32_bf16 v[56:59], v[158:161], v[178:181], v[56:59]
	v_mfma_f32_16x16x32_bf16 v[60:63], v[162:165], v[178:181], v[60:63]
	s_waitcnt lgkmcnt(3)
	v_mfma_f32_16x16x32_bf16 v[72:75], v[158:161], v[222:225], v[72:75]
	v_mfma_f32_16x16x32_bf16 v[76:79], v[162:165], v[222:225], v[76:79]
	s_waitcnt lgkmcnt(2)
	s_mov_b32 m0, s44
	v_mfma_f32_16x16x32_bf16 v[48:51], v[214:217], v[166:169], v[48:51]
	global_load_lds_dwordx4 v146, s[48:49]
	s_waitcnt lgkmcnt(1)
	v_mfma_f32_16x16x32_bf16 v[174:177], v[218:221], v[166:169], v[174:177]
	ds_read_b128 v[166:169], v6 offset:9216
	v_mfma_f32_16x16x32_bf16 v[64:67], v[214:217], v[178:181], v[64:67]
	v_mfma_f32_16x16x32_bf16 v[170:173], v[218:221], v[178:181], v[170:173]
	ds_read_b128 v[178:181], v6 offset:11264
	v_mfma_f32_16x16x32_bf16 v[80:83], v[214:217], v[222:225], v[80:83]
	v_mfma_f32_16x16x32_bf16 v[32:35], v[218:221], v[222:225], v[32:35]
	ds_read_b128 v[222:225], v6 offset:13312
	s_waitcnt lgkmcnt(3)
	v_mfma_f32_16x16x32_bf16 v[88:91], v[158:161], v[226:229], v[88:91]
	v_mfma_f32_16x16x32_bf16 v[92:95], v[162:165], v[226:229], v[92:95]
	v_mfma_f32_16x16x32_bf16 v[96:99], v[214:217], v[226:229], v[96:99]
	v_mfma_f32_16x16x32_bf16 v[36:39], v[218:221], v[226:229], v[36:39]
	ds_read_b128 v[226:229], v6 offset:15360
	s_waitcnt lgkmcnt(3)
	v_mfma_f32_16x16x32_bf16 v[104:107], v[158:161], v[166:169], v[104:107]
	v_mfma_f32_16x16x32_bf16 v[108:111], v[162:165], v[166:169], v[108:111]
	v_mfma_f32_16x16x32_bf16 v[112:115], v[214:217], v[166:169], v[112:115]
	v_mfma_f32_16x16x32_bf16 v[52:55], v[218:221], v[166:169], v[52:55]
	s_waitcnt lgkmcnt(2)
	v_mfma_f32_16x16x32_bf16 v[116:119], v[158:161], v[178:181], v[116:119]
	v_mfma_f32_16x16x32_bf16 v[120:123], v[162:165], v[178:181], v[120:123]
	v_mfma_f32_16x16x32_bf16 v[124:127], v[214:217], v[178:181], v[124:127]
	v_mfma_f32_16x16x32_bf16 v[68:71], v[218:221], v[178:181], v[68:71]
	s_waitcnt lgkmcnt(1)
	v_mfma_f32_16x16x32_bf16 v[128:131], v[158:161], v[222:225], v[128:131]
	v_mfma_f32_16x16x32_bf16 v[132:135], v[162:165], v[222:225], v[132:135]
	v_mfma_f32_16x16x32_bf16 v[136:139], v[214:217], v[222:225], v[136:139]
	v_mfma_f32_16x16x32_bf16 v[84:87], v[218:221], v[222:225], v[84:87]
	s_waitcnt lgkmcnt(0)
	v_mfma_f32_16x16x32_bf16 v[100:103], v[158:161], v[226:229], v[100:103]
	v_mfma_f32_16x16x32_bf16 v[140:143], v[162:165], v[226:229], v[140:143]
	v_mfma_f32_16x16x32_bf16 v[150:153], v[214:217], v[226:229], v[150:153]
	v_mfma_f32_16x16x32_bf16 v[154:157], v[218:221], v[226:229], v[154:157]
	s_add_u32 s46, s16, 0xf00
	s_addc_u32 s47, s17, 0
	s_add_u32 s48, s18, 0xf00
	s_waitcnt vmcnt(0)
	s_barrier
	s_addc_u32 s49, s19, 0
	v_lshl_add_u64 v[158:159], s[46:47], 0, v[0:1]
	s_mov_b32 s45, m0
	s_mov_b32 m0, s1
	s_nop 0
	global_load_lds_dwordx4 v[158:159], off
	s_mov_b32 m0, s45
	v_lshl_add_u64 v[158:159], s[48:49], 0, v[0:1]
	s_mov_b32 s45, m0
	s_mov_b32 m0, s30
	s_nop 0
	global_load_lds_dwordx4 v[158:159], off
	s_mov_b32 m0, s45
	v_lshl_add_u64 v[158:159], s[46:47], 0, v[2:3]
	s_mov_b32 s45, m0
	s_mov_b32 m0, s31
	s_nop 0
	global_load_lds_dwordx4 v[158:159], off
	s_mov_b32 m0, s45
	v_lshl_add_u64 v[158:159], s[48:49], 0, v[2:3]
	s_mov_b32 s45, m0
	s_mov_b32 m0, s34
	s_nop 0
	global_load_lds_dwordx4 v[158:159], off
	s_mov_b32 m0, s45
	v_lshl_add_u64 v[158:159], s[46:47], 0, v[4:5]
	s_mov_b32 s45, m0
	s_mov_b32 m0, s35
	s_nop 0
	global_load_lds_dwordx4 v[158:159], off
	s_mov_b32 m0, s45
	v_lshl_add_u64 v[158:159], s[48:49], 0, v[4:5]
	s_mov_b32 s45, m0
	s_mov_b32 m0, s36
	s_nop 0
	global_load_lds_dwordx4 v[158:159], off
	s_mov_b32 m0, s45
	v_lshl_add_u64 v[158:159], s[46:47], 0, v[146:147]
	s_mov_b32 s45, m0
	s_mov_b32 m0, s37
	s_nop 0
	global_load_lds_dwordx4 v[158:159], off
	s_mov_b32 m0, s45
	v_lshl_add_u64 v[158:159], s[48:49], 0, v[146:147]
	s_mov_b32 s45, m0
	s_mov_b32 m0, s38
	s_nop 0
	global_load_lds_dwordx4 v[158:159], off
	s_mov_b32 m0, s45
	ds_read_b128 v[158:161], v8
	ds_read_b128 v[162:165], v9
	ds_read_b128 v[166:169], v11
	ds_read_b128 v[214:217], v10
	ds_read_b128 v[178:181], v12
	ds_read_b128 v[218:221], v13
	ds_read_b128 v[222:225], v14
	ds_read_b128 v[226:229], v15
	s_waitcnt lgkmcnt(3)
	v_mfma_f32_16x16x32_bf16 v[40:43], v[158:161], v[178:181], v[40:43]
	v_mfma_f32_16x16x32_bf16 v[44:47], v[162:165], v[178:181], v[44:47]
	v_mfma_f32_16x16x32_bf16 v[48:51], v[166:169], v[178:181], v[48:51]
	v_mfma_f32_16x16x32_bf16 v[174:177], v[214:217], v[178:181], v[174:177]
	ds_read_b128 v[178:181], v16
	s_waitcnt lgkmcnt(3)
	v_mfma_f32_16x16x32_bf16 v[56:59], v[158:161], v[218:221], v[56:59]
	v_mfma_f32_16x16x32_bf16 v[60:63], v[162:165], v[218:221], v[60:63]
	v_mfma_f32_16x16x32_bf16 v[64:67], v[166:169], v[218:221], v[64:67]
	v_mfma_f32_16x16x32_bf16 v[170:173], v[214:217], v[218:221], v[170:173]
	ds_read_b128 v[218:221], v17
	s_waitcnt lgkmcnt(3)
	v_mfma_f32_16x16x32_bf16 v[72:75], v[158:161], v[222:225], v[72:75]
	v_mfma_f32_16x16x32_bf16 v[76:79], v[162:165], v[222:225], v[76:79]
	v_mfma_f32_16x16x32_bf16 v[80:83], v[166:169], v[222:225], v[80:83]
	v_mfma_f32_16x16x32_bf16 v[32:35], v[214:217], v[222:225], v[32:35]
	ds_read_b128 v[222:225], v18
	s_waitcnt lgkmcnt(3)
	v_mfma_f32_16x16x32_bf16 v[88:91], v[158:161], v[226:229], v[88:91]
	v_mfma_f32_16x16x32_bf16 v[92:95], v[162:165], v[226:229], v[92:95]
	v_mfma_f32_16x16x32_bf16 v[96:99], v[166:169], v[226:229], v[96:99]
	v_mfma_f32_16x16x32_bf16 v[36:39], v[214:217], v[226:229], v[36:39]
	ds_read_b128 v[226:229], v19
	s_waitcnt lgkmcnt(3)
	v_mfma_f32_16x16x32_bf16 v[104:107], v[158:161], v[178:181], v[104:107]
	v_mfma_f32_16x16x32_bf16 v[108:111], v[162:165], v[178:181], v[108:111]
	v_mfma_f32_16x16x32_bf16 v[112:115], v[166:169], v[178:181], v[112:115]
	v_mfma_f32_16x16x32_bf16 v[52:55], v[214:217], v[178:181], v[52:55]
	s_waitcnt lgkmcnt(2)
	v_mfma_f32_16x16x32_bf16 v[116:119], v[158:161], v[218:221], v[116:119]
	v_mfma_f32_16x16x32_bf16 v[120:123], v[162:165], v[218:221], v[120:123]
	v_mfma_f32_16x16x32_bf16 v[124:127], v[166:169], v[218:221], v[124:127]
	v_mfma_f32_16x16x32_bf16 v[68:71], v[214:217], v[218:221], v[68:71]
	s_waitcnt lgkmcnt(1)
	v_mfma_f32_16x16x32_bf16 v[132:135], v[162:165], v[222:225], v[132:135]
	v_mfma_f32_16x16x32_bf16 v[84:87], v[214:217], v[222:225], v[84:87]
	s_waitcnt lgkmcnt(0)
	v_mfma_f32_16x16x32_bf16 v[100:103], v[158:161], v[226:229], v[100:103]
	v_mfma_f32_16x16x32_bf16 v[150:153], v[166:169], v[226:229], v[150:153]
	v_mfma_f32_16x16x32_bf16 v[154:157], v[214:217], v[226:229], v[154:157]
	v_mfma_f32_16x16x32_bf16 v[128:131], v[158:161], v[222:225], v[128:131]
	v_mfma_f32_16x16x32_bf16 v[136:139], v[166:169], v[222:225], v[136:139]
	v_mfma_f32_16x16x32_bf16 v[140:143], v[162:165], v[226:229], v[140:143]
	ds_read_b128 v[158:161], v20
	ds_read_b128 v[162:165], v21
	ds_read_b128 v[166:169], v23
	ds_read_b128 v[214:217], v22
	ds_read_b128 v[178:181], v24
	ds_read_b128 v[218:221], v25
	ds_read_b128 v[222:225], v26
	ds_read_b128 v[226:229], v27
	s_waitcnt lgkmcnt(3)
	v_mfma_f32_16x16x32_bf16 v[40:43], v[158:161], v[178:181], v[40:43]
	v_mfma_f32_16x16x32_bf16 v[44:47], v[162:165], v[178:181], v[44:47]
	v_mfma_f32_16x16x32_bf16 v[48:51], v[166:169], v[178:181], v[48:51]
	v_mfma_f32_16x16x32_bf16 v[174:177], v[214:217], v[178:181], v[174:177]
	ds_read_b128 v[178:181], v28
	s_waitcnt lgkmcnt(3)
	v_mfma_f32_16x16x32_bf16 v[56:59], v[158:161], v[218:221], v[56:59]
	v_mfma_f32_16x16x32_bf16 v[60:63], v[162:165], v[218:221], v[60:63]
	v_mfma_f32_16x16x32_bf16 v[64:67], v[166:169], v[218:221], v[64:67]
	v_mfma_f32_16x16x32_bf16 v[170:173], v[214:217], v[218:221], v[170:173]
	ds_read_b128 v[218:221], v29
	s_waitcnt lgkmcnt(3)
	v_mfma_f32_16x16x32_bf16 v[72:75], v[158:161], v[222:225], v[72:75]
	v_mfma_f32_16x16x32_bf16 v[76:79], v[162:165], v[222:225], v[76:79]
	v_mfma_f32_16x16x32_bf16 v[80:83], v[166:169], v[222:225], v[80:83]
	v_mfma_f32_16x16x32_bf16 v[32:35], v[214:217], v[222:225], v[32:35]
	ds_read_b128 v[222:225], v30
	s_waitcnt lgkmcnt(3)
	v_mfma_f32_16x16x32_bf16 v[88:91], v[158:161], v[226:229], v[88:91]
	v_mfma_f32_16x16x32_bf16 v[92:95], v[162:165], v[226:229], v[92:95]
	v_mfma_f32_16x16x32_bf16 v[96:99], v[166:169], v[226:229], v[96:99]
	v_mfma_f32_16x16x32_bf16 v[36:39], v[214:217], v[226:229], v[36:39]
	ds_read_b128 v[226:229], v31
	s_waitcnt lgkmcnt(3)
	v_mfma_f32_16x16x32_bf16 v[104:107], v[158:161], v[178:181], v[104:107]
	v_mfma_f32_16x16x32_bf16 v[108:111], v[162:165], v[178:181], v[108:111]
	v_mfma_f32_16x16x32_bf16 v[112:115], v[166:169], v[178:181], v[112:115]
	v_mfma_f32_16x16x32_bf16 v[52:55], v[214:217], v[178:181], v[52:55]
	s_waitcnt lgkmcnt(2)
	v_mfma_f32_16x16x32_bf16 v[116:119], v[158:161], v[218:221], v[116:119]
	v_mfma_f32_16x16x32_bf16 v[120:123], v[162:165], v[218:221], v[120:123]
	v_mfma_f32_16x16x32_bf16 v[124:127], v[166:169], v[218:221], v[124:127]
	v_mfma_f32_16x16x32_bf16 v[68:71], v[214:217], v[218:221], v[68:71]
	s_waitcnt lgkmcnt(1)
	v_mfma_f32_16x16x32_bf16 v[132:135], v[162:165], v[222:225], v[132:135]
	v_mfma_f32_16x16x32_bf16 v[84:87], v[214:217], v[222:225], v[84:87]
	s_waitcnt lgkmcnt(0)
	v_mfma_f32_16x16x32_bf16 v[100:103], v[158:161], v[226:229], v[100:103]
	v_mfma_f32_16x16x32_bf16 v[150:153], v[166:169], v[226:229], v[150:153]
	v_mfma_f32_16x16x32_bf16 v[154:157], v[214:217], v[226:229], v[154:157]
	v_mfma_f32_16x16x32_bf16 v[128:131], v[158:161], v[222:225], v[128:131]
	v_mfma_f32_16x16x32_bf16 v[136:139], v[166:169], v[222:225], v[136:139]
	v_mfma_f32_16x16x32_bf16 v[140:143], v[162:165], v[226:229], v[140:143]
	s_add_u32 s16, s16, 0xf80
	s_addc_u32 s17, s17, 0
	s_add_u32 s18, s18, 0xf80
	s_waitcnt vmcnt(0)
	s_barrier
	s_addc_u32 s19, s19, 0
	v_lshl_add_u64 v[158:159], s[16:17], 0, v[0:1]
	s_mov_b32 s45, m0
	s_mov_b32 m0, s25
	s_nop 0
	global_load_lds_dwordx4 v[158:159], off
	s_mov_b32 m0, s45
	v_lshl_add_u64 v[158:159], s[18:19], 0, v[0:1]
	s_mov_b32 s25, m0
	s_mov_b32 m0, s24
	s_nop 0
	global_load_lds_dwordx4 v[158:159], off
	s_mov_b32 m0, s25
	v_lshl_add_u64 v[158:159], s[16:17], 0, v[2:3]
	s_mov_b32 s24, m0
	s_mov_b32 m0, s39
	s_nop 0
	global_load_lds_dwordx4 v[158:159], off
	s_mov_b32 m0, s24
	v_lshl_add_u64 v[158:159], s[18:19], 0, v[2:3]
	s_mov_b32 s24, m0
	s_mov_b32 m0, s40
	s_nop 0
	global_load_lds_dwordx4 v[158:159], off
	s_mov_b32 m0, s24
	v_lshl_add_u64 v[158:159], s[16:17], 0, v[4:5]
	s_mov_b32 s24, m0
	s_mov_b32 m0, s41
	s_nop 0
	global_load_lds_dwordx4 v[158:159], off
	s_mov_b32 m0, s24
	v_lshl_add_u64 v[158:159], s[18:19], 0, v[4:5]
	s_mov_b32 s24, m0
	s_mov_b32 m0, s42
	s_nop 0
	global_load_lds_dwordx4 v[158:159], off
	s_mov_b32 m0, s24
	v_lshl_add_u64 v[158:159], s[16:17], 0, v[146:147]
	s_mov_b32 s16, m0
	s_mov_b32 m0, s43
	s_nop 0
	global_load_lds_dwordx4 v[158:159], off
	s_mov_b32 m0, s16
	v_lshl_add_u64 v[158:159], s[18:19], 0, v[146:147]
	s_mov_b32 s16, m0
	s_mov_b32 m0, s44
	s_nop 0
	global_load_lds_dwordx4 v[158:159], off
	s_mov_b32 m0, s16
	ds_read_b128 v[158:161], v7 offset:32768
	ds_read_b128 v[162:165], v7 offset:34816
	ds_read_b128 v[166:169], v7 offset:36864
	ds_read_b128 v[214:217], v7 offset:38912
	ds_read_b128 v[178:181], v6
	ds_read_b128 v[218:221], v6 offset:2048
	ds_read_b128 v[222:225], v6 offset:4096
	ds_read_b128 v[226:229], v6 offset:6144
	s_waitcnt lgkmcnt(3)
	v_mfma_f32_16x16x32_bf16 v[40:43], v[158:161], v[178:181], v[40:43]
	v_mfma_f32_16x16x32_bf16 v[44:47], v[162:165], v[178:181], v[44:47]
	v_mfma_f32_16x16x32_bf16 v[48:51], v[166:169], v[178:181], v[48:51]
	v_mfma_f32_16x16x32_bf16 v[174:177], v[214:217], v[178:181], v[174:177]
	ds_read_b128 v[178:181], v6 offset:8192
	s_waitcnt lgkmcnt(3)
	v_mfma_f32_16x16x32_bf16 v[56:59], v[158:161], v[218:221], v[56:59]
	v_mfma_f32_16x16x32_bf16 v[60:63], v[162:165], v[218:221], v[60:63]
	v_mfma_f32_16x16x32_bf16 v[64:67], v[166:169], v[218:221], v[64:67]
	v_mfma_f32_16x16x32_bf16 v[170:173], v[214:217], v[218:221], v[170:173]
	ds_read_b128 v[218:221], v6 offset:10240
	s_waitcnt lgkmcnt(3)
	v_mfma_f32_16x16x32_bf16 v[72:75], v[158:161], v[222:225], v[72:75]
	v_mfma_f32_16x16x32_bf16 v[76:79], v[162:165], v[222:225], v[76:79]
	v_mfma_f32_16x16x32_bf16 v[80:83], v[166:169], v[222:225], v[80:83]
	v_mfma_f32_16x16x32_bf16 v[32:35], v[214:217], v[222:225], v[32:35]
	ds_read_b128 v[222:225], v6 offset:12288
	s_waitcnt lgkmcnt(3)
	v_mfma_f32_16x16x32_bf16 v[88:91], v[158:161], v[226:229], v[88:91]
	v_mfma_f32_16x16x32_bf16 v[92:95], v[162:165], v[226:229], v[92:95]
	v_mfma_f32_16x16x32_bf16 v[96:99], v[166:169], v[226:229], v[96:99]
	v_mfma_f32_16x16x32_bf16 v[36:39], v[214:217], v[226:229], v[36:39]
	ds_read_b128 v[226:229], v6 offset:14336
	s_waitcnt lgkmcnt(3)
	v_mfma_f32_16x16x32_bf16 v[104:107], v[158:161], v[178:181], v[104:107]
	v_mfma_f32_16x16x32_bf16 v[108:111], v[162:165], v[178:181], v[108:111]
	v_mfma_f32_16x16x32_bf16 v[112:115], v[166:169], v[178:181], v[112:115]
	v_mfma_f32_16x16x32_bf16 v[52:55], v[214:217], v[178:181], v[52:55]
	s_waitcnt lgkmcnt(2)
	v_mfma_f32_16x16x32_bf16 v[116:119], v[158:161], v[218:221], v[116:119]
	v_mfma_f32_16x16x32_bf16 v[120:123], v[162:165], v[218:221], v[120:123]
	v_mfma_f32_16x16x32_bf16 v[124:127], v[166:169], v[218:221], v[124:127]
	v_mfma_f32_16x16x32_bf16 v[68:71], v[214:217], v[218:221], v[68:71]
	s_waitcnt lgkmcnt(1)
	v_mfma_f32_16x16x32_bf16 v[132:135], v[162:165], v[222:225], v[132:135]
	v_mfma_f32_16x16x32_bf16 v[84:87], v[214:217], v[222:225], v[84:87]
	s_waitcnt lgkmcnt(0)
	v_mfma_f32_16x16x32_bf16 v[100:103], v[158:161], v[226:229], v[100:103]
	v_mfma_f32_16x16x32_bf16 v[150:153], v[166:169], v[226:229], v[150:153]
	v_mfma_f32_16x16x32_bf16 v[154:157], v[214:217], v[226:229], v[154:157]
	v_mfma_f32_16x16x32_bf16 v[128:131], v[158:161], v[222:225], v[128:131]
	v_mfma_f32_16x16x32_bf16 v[136:139], v[166:169], v[222:225], v[136:139]
	v_mfma_f32_16x16x32_bf16 v[140:143], v[162:165], v[226:229], v[140:143]
	ds_read_b128 v[158:161], v7 offset:33792
	ds_read_b128 v[162:165], v7 offset:35840
	ds_read_b128 v[166:169], v7 offset:37888
	ds_read_b128 v[214:217], v7 offset:39936
	ds_read_b128 v[178:181], v6 offset:1024
	ds_read_b128 v[218:221], v6 offset:3072
	ds_read_b128 v[222:225], v6 offset:5120
	ds_read_b128 v[226:229], v6 offset:7168
	s_waitcnt lgkmcnt(3)
	v_mfma_f32_16x16x32_bf16 v[40:43], v[158:161], v[178:181], v[40:43]
	v_mfma_f32_16x16x32_bf16 v[44:47], v[162:165], v[178:181], v[44:47]
	v_mfma_f32_16x16x32_bf16 v[48:51], v[166:169], v[178:181], v[48:51]
	v_mfma_f32_16x16x32_bf16 v[174:177], v[214:217], v[178:181], v[174:177]
	ds_read_b128 v[178:181], v6 offset:9216
	s_waitcnt lgkmcnt(3)
	v_mfma_f32_16x16x32_bf16 v[56:59], v[158:161], v[218:221], v[56:59]
	v_mfma_f32_16x16x32_bf16 v[60:63], v[162:165], v[218:221], v[60:63]
	v_mfma_f32_16x16x32_bf16 v[64:67], v[166:169], v[218:221], v[64:67]
	v_mfma_f32_16x16x32_bf16 v[170:173], v[214:217], v[218:221], v[170:173]
	ds_read_b128 v[218:221], v6 offset:11264
	s_waitcnt lgkmcnt(3)
	v_mfma_f32_16x16x32_bf16 v[72:75], v[158:161], v[222:225], v[72:75]
	v_mfma_f32_16x16x32_bf16 v[76:79], v[162:165], v[222:225], v[76:79]
	v_mfma_f32_16x16x32_bf16 v[80:83], v[166:169], v[222:225], v[80:83]
	v_mfma_f32_16x16x32_bf16 v[32:35], v[214:217], v[222:225], v[32:35]
	ds_read_b128 v[222:225], v6 offset:13312
	s_waitcnt lgkmcnt(3)
	v_mfma_f32_16x16x32_bf16 v[88:91], v[158:161], v[226:229], v[88:91]
	v_mfma_f32_16x16x32_bf16 v[92:95], v[162:165], v[226:229], v[92:95]
	v_mfma_f32_16x16x32_bf16 v[96:99], v[166:169], v[226:229], v[96:99]
	v_mfma_f32_16x16x32_bf16 v[36:39], v[214:217], v[226:229], v[36:39]
	ds_read_b128 v[226:229], v6 offset:15360
	s_waitcnt lgkmcnt(3)
	v_mfma_f32_16x16x32_bf16 v[104:107], v[158:161], v[178:181], v[104:107]
	v_mfma_f32_16x16x32_bf16 v[108:111], v[162:165], v[178:181], v[108:111]
	v_mfma_f32_16x16x32_bf16 v[112:115], v[166:169], v[178:181], v[112:115]
	v_mfma_f32_16x16x32_bf16 v[52:55], v[214:217], v[178:181], v[52:55]
	s_waitcnt lgkmcnt(2)
	v_mfma_f32_16x16x32_bf16 v[116:119], v[158:161], v[218:221], v[116:119]
	v_mfma_f32_16x16x32_bf16 v[120:123], v[162:165], v[218:221], v[120:123]
	v_mfma_f32_16x16x32_bf16 v[124:127], v[166:169], v[218:221], v[124:127]
	v_mfma_f32_16x16x32_bf16 v[68:71], v[214:217], v[218:221], v[68:71]
	s_waitcnt lgkmcnt(1)
	v_mfma_f32_16x16x32_bf16 v[132:135], v[162:165], v[222:225], v[132:135]
	v_mfma_f32_16x16x32_bf16 v[84:87], v[214:217], v[222:225], v[84:87]
	s_waitcnt lgkmcnt(0)
	v_mfma_f32_16x16x32_bf16 v[100:103], v[158:161], v[226:229], v[100:103]
	v_mfma_f32_16x16x32_bf16 v[150:153], v[166:169], v[226:229], v[150:153]
	v_mfma_f32_16x16x32_bf16 v[154:157], v[214:217], v[226:229], v[154:157]
	v_mfma_f32_16x16x32_bf16 v[128:131], v[158:161], v[222:225], v[128:131]
	v_mfma_f32_16x16x32_bf16 v[136:139], v[166:169], v[222:225], v[136:139]
	v_mfma_f32_16x16x32_bf16 v[140:143], v[162:165], v[226:229], v[140:143]
	s_waitcnt vmcnt(0)
	s_barrier
	v_lshl_add_u64 v[6:7], s[20:21], 0, v[0:1]
	s_mov_b32 s16, m0
	s_mov_b32 m0, s1
	s_nop 0
	global_load_lds_dwordx4 v[6:7], off
	s_mov_b32 m0, s16
	v_lshl_add_u64 v[0:1], s[22:23], 0, v[0:1]
	s_mov_b32 s1, m0
	s_mov_b32 m0, s30
	s_nop 0
	global_load_lds_dwordx4 v[0:1], off
	s_mov_b32 m0, s1
	v_lshl_add_u64 v[0:1], s[20:21], 0, v[2:3]
	s_mov_b32 s1, m0
	s_mov_b32 m0, s31
	s_nop 0
	global_load_lds_dwordx4 v[0:1], off
	s_mov_b32 m0, s1
	v_lshl_add_u64 v[0:1], s[22:23], 0, v[2:3]
	s_mov_b32 s1, m0
	s_mov_b32 m0, s34
	s_nop 0
	global_load_lds_dwordx4 v[0:1], off
	s_mov_b32 m0, s1
	v_lshl_add_u64 v[0:1], s[20:21], 0, v[4:5]
	s_mov_b32 s1, m0
	s_mov_b32 m0, s35
	s_nop 0
	global_load_lds_dwordx4 v[0:1], off
	s_mov_b32 m0, s1
	v_lshl_add_u64 v[0:1], s[22:23], 0, v[4:5]
	s_mov_b32 s1, m0
	s_mov_b32 m0, s36
	s_nop 0
	global_load_lds_dwordx4 v[0:1], off
	s_mov_b32 m0, s1
	v_lshl_add_u64 v[0:1], s[20:21], 0, v[146:147]
	s_mov_b32 s1, m0
	s_mov_b32 m0, s37
	s_nop 0
	global_load_lds_dwordx4 v[0:1], off
	s_mov_b32 m0, s1
	v_lshl_add_u64 v[0:1], s[22:23], 0, v[146:147]
	s_mov_b32 s1, m0
	s_mov_b32 m0, s38
	s_nop 0
	global_load_lds_dwordx4 v[0:1], off
	s_mov_b32 m0, s1
	ds_read_b128 v[0:3], v8
	ds_read_b128 v[4:7], v9
	ds_read_b128 v[158:161], v11
	ds_read_b128 v[8:11], v10
	ds_read_b128 v[162:165], v12
	ds_read_b128 v[166:169], v13
	ds_read_b128 v[178:181], v14
	ds_read_b128 v[12:15], v15
	s_waitcnt lgkmcnt(3)
	v_mfma_f32_16x16x32_bf16 v[40:43], v[0:3], v[162:165], v[40:43]
	v_mfma_f32_16x16x32_bf16 v[44:47], v[4:7], v[162:165], v[44:47]
	v_mfma_f32_16x16x32_bf16 v[48:51], v[158:161], v[162:165], v[48:51]
	v_mfma_f32_16x16x32_bf16 v[162:165], v[8:11], v[162:165], v[174:177]
	s_nop 2
	ds_read_b128 v[174:177], v16
	s_waitcnt lgkmcnt(3)
	v_mfma_f32_16x16x32_bf16 v[56:59], v[0:3], v[166:169], v[56:59]
	v_mfma_f32_16x16x32_bf16 v[60:63], v[4:7], v[166:169], v[60:63]
	v_mfma_f32_16x16x32_bf16 v[64:67], v[158:161], v[166:169], v[64:67]
	v_mfma_f32_16x16x32_bf16 v[166:169], v[8:11], v[166:169], v[170:173]
	s_nop 2
	ds_read_b128 v[170:173], v17
	s_waitcnt lgkmcnt(3)
	v_mfma_f32_16x16x32_bf16 v[72:75], v[0:3], v[178:181], v[72:75]
	v_mfma_f32_16x16x32_bf16 v[76:79], v[4:7], v[178:181], v[76:79]
	v_mfma_f32_16x16x32_bf16 v[80:83], v[158:161], v[178:181], v[80:83]
	v_mfma_f32_16x16x32_bf16 v[32:35], v[8:11], v[178:181], v[32:35]
	ds_read_b128 v[178:181], v18
	s_waitcnt lgkmcnt(3)
	v_mfma_f32_16x16x32_bf16 v[214:217], v[0:3], v[12:15], v[88:91]
	v_mfma_f32_16x16x32_bf16 v[218:221], v[4:7], v[12:15], v[92:95]
	v_mfma_f32_16x16x32_bf16 v[222:225], v[158:161], v[12:15], v[96:99]
	v_mfma_f32_16x16x32_bf16 v[12:15], v[8:11], v[12:15], v[36:39]
	ds_read_b128 v[16:19], v19
	s_waitcnt lgkmcnt(3)
	v_mfma_f32_16x16x32_bf16 v[36:39], v[0:3], v[174:177], v[104:107]
	v_mfma_f32_16x16x32_bf16 v[226:229], v[4:7], v[174:177], v[108:111]
	v_mfma_f32_16x16x32_bf16 v[112:115], v[158:161], v[174:177], v[112:115]
	s_waitcnt lgkmcnt(2)
	v_mfma_f32_16x16x32_bf16 v[116:119], v[0:3], v[170:173], v[116:119]
	v_mfma_f32_16x16x32_bf16 v[120:123], v[4:7], v[170:173], v[120:123]
	v_mfma_f32_16x16x32_bf16 v[124:127], v[158:161], v[170:173], v[124:127]
	s_waitcnt lgkmcnt(1)
	v_mfma_f32_16x16x32_bf16 v[128:131], v[0:3], v[178:181], v[128:131]
	v_mfma_f32_16x16x32_bf16 v[132:135], v[4:7], v[178:181], v[132:135]
	s_waitcnt lgkmcnt(0)
	v_mfma_f32_16x16x32_bf16 v[0:3], v[0:3], v[16:19], v[100:103]
	v_mfma_f32_16x16x32_bf16 v[4:7], v[4:7], v[16:19], v[140:143]
	v_mfma_f32_16x16x32_bf16 v[140:143], v[158:161], v[16:19], v[150:153]
	v_mfma_f32_16x16x32_bf16 v[150:153], v[8:11], v[16:19], v[154:157]
	v_mfma_f32_16x16x32_bf16 v[174:177], v[8:11], v[174:177], v[52:55]
	v_mfma_f32_16x16x32_bf16 v[170:173], v[8:11], v[170:173], v[68:71]
	v_mfma_f32_16x16x32_bf16 v[136:139], v[158:161], v[178:181], v[136:139]
	v_mfma_f32_16x16x32_bf16 v[178:181], v[8:11], v[178:181], v[84:87]
	ds_read_b128 v[8:11], v20
	ds_read_b128 v[154:157], v21
	ds_read_b128 v[158:161], v23
	ds_read_b128 v[230:233], v22
	ds_read_b128 v[16:19], v24
	ds_read_b128 v[20:23], v25
	ds_read_b128 v[52:55], v26
	ds_read_b128 v[24:27], v27
	s_waitcnt lgkmcnt(3)
	v_mfma_f32_16x16x32_bf16 v[234:237], v[8:11], v[16:19], v[40:43]
	v_mfma_f32_16x16x32_bf16 v[238:241], v[154:157], v[16:19], v[44:47]
	v_mfma_f32_16x16x32_bf16 v[242:245], v[158:161], v[16:19], v[48:51]
	v_mfma_f32_16x16x32_bf16 v[162:165], v[230:233], v[16:19], v[162:165]
	ds_read_b128 v[16:19], v28
	s_waitcnt lgkmcnt(3)
	v_mfma_f32_16x16x32_bf16 v[108:111], v[8:11], v[20:23], v[56:59]
	v_mfma_f32_16x16x32_bf16 v[104:107], v[154:157], v[20:23], v[60:63]
	v_mfma_f32_16x16x32_bf16 v[100:103], v[158:161], v[20:23], v[64:67]
	v_mfma_f32_16x16x32_bf16 v[96:99], v[230:233], v[20:23], v[166:169]
	ds_read_b128 v[20:23], v29
	s_waitcnt lgkmcnt(3)
	v_mfma_f32_16x16x32_bf16 v[92:95], v[8:11], v[52:55], v[72:75]
	v_mfma_f32_16x16x32_bf16 v[88:91], v[154:157], v[52:55], v[76:79]
	v_mfma_f32_16x16x32_bf16 v[84:87], v[158:161], v[52:55], v[80:83]
	v_mfma_f32_16x16x32_bf16 v[80:83], v[230:233], v[52:55], v[32:35]
	ds_read_b128 v[166:169], v30
	s_waitcnt lgkmcnt(3)
	v_mfma_f32_16x16x32_bf16 v[76:79], v[8:11], v[24:27], v[214:217]
	v_mfma_f32_16x16x32_bf16 v[72:75], v[154:157], v[24:27], v[218:221]
	v_mfma_f32_16x16x32_bf16 v[68:71], v[158:161], v[24:27], v[222:225]
	v_mfma_f32_16x16x32_bf16 v[64:67], v[230:233], v[24:27], v[12:15]
	ds_read_b128 v[214:217], v31
	s_waitcnt lgkmcnt(3)
	v_mfma_f32_16x16x32_bf16 v[60:63], v[8:11], v[16:19], v[36:39]
	v_mfma_f32_16x16x32_bf16 v[56:59], v[154:157], v[16:19], v[226:229]
	v_mfma_f32_16x16x32_bf16 v[52:55], v[158:161], v[16:19], v[112:115]
	v_mfma_f32_16x16x32_bf16 v[48:51], v[230:233], v[16:19], v[174:177]
	s_waitcnt lgkmcnt(2)
	v_mfma_f32_16x16x32_bf16 v[44:47], v[8:11], v[20:23], v[116:119]
	v_mfma_f32_16x16x32_bf16 v[40:43], v[154:157], v[20:23], v[120:123]
	v_mfma_f32_16x16x32_bf16 v[36:39], v[158:161], v[20:23], v[124:127]
	v_mfma_f32_16x16x32_bf16 v[32:35], v[230:233], v[20:23], v[170:173]
	s_waitcnt lgkmcnt(1)
	v_mfma_f32_16x16x32_bf16 v[28:31], v[8:11], v[166:169], v[128:131]
	v_mfma_f32_16x16x32_bf16 v[24:27], v[154:157], v[166:169], v[132:135]
	v_mfma_f32_16x16x32_bf16 v[20:23], v[158:161], v[166:169], v[136:139]
	v_mfma_f32_16x16x32_bf16 v[16:19], v[230:233], v[166:169], v[178:181]
	s_waitcnt lgkmcnt(0)
	v_mfma_f32_16x16x32_bf16 v[12:15], v[8:11], v[214:217], v[0:3]
	v_mfma_f32_16x16x32_bf16 v[8:11], v[154:157], v[214:217], v[4:7]
	v_mfma_f32_16x16x32_bf16 v[4:7], v[158:161], v[214:217], v[140:143]
	v_mfma_f32_16x16x32_bf16 v[0:3], v[230:233], v[214:217], v[150:153]
	v_mov_b32_e32 v145, v184
	s_waitcnt vmcnt(0)
	s_barrier
	s_lshl_b32 s18, s0, 8
	s_lshl_b32 s16, s14, 8
	v_and_b32_e32 v151, 15, v145
	v_ashrrev_i32_e32 v112, 1, v145
	v_and_b32_e32 v153, 0xffffff80, v112
	v_or_b32_e32 v112, s18, v151
	v_add_u32_e32 v112, v112, v153
	v_ashrrev_i32_e32 v113, 31, v112
	v_lshlrev_b64 v[112:113], 13, v[112:113]
	v_bfe_u32 v150, v145, 6, 2
	v_lshl_add_u64 v[112:113], s[2:3], 0, v[112:113]
	s_ashr_i32 s17, s16, 31
	v_bfe_u32 v152, v145, 4, 2
	v_lshl_add_u64 v[112:113], s[16:17], 2, v[112:113]
	v_lshlrev_b32_e32 v146, 8, v150
	v_lshl_add_u64 v[112:113], v[112:113], 0, v[146:147]
	v_lshlrev_b32_e32 v146, 4, v152
	v_lshl_add_u64 v[154:155], v[112:113], 0, v[146:147]
	global_load_dwordx4 v[120:123], v[154:155], off offset:192
	global_load_dwordx4 v[128:131], v[154:155], off offset:128
	global_load_dwordx4 v[136:139], v[154:155], off offset:64
	global_load_dwordx4 v[140:143], v[154:155], off
	v_add_co_u32_e32 v112, vcc, s66, v154
	v_lshlrev_b32_e32 v158, 2, v152
	s_nop 0
	v_addc_co_u32_e32 v113, vcc, 0, v155, vcc
	global_load_dwordx4 v[132:135], v[112:113], off
	global_load_dwordx4 v[124:127], v[112:113], off offset:64
	global_load_dwordx4 v[116:119], v[112:113], off offset:128
	v_cmp_lt_i32_e32 vcc, v188, v186
	global_load_dwordx4 v[112:115], v[112:113], off offset:192
	v_cmp_eq_u32_e64 s[0:1], 0, v152
	v_cndmask_b32_e32 v146, v185, v188, vcc
	v_cmp_lt_i32_e32 vcc, v187, v186
	v_lshlrev_b32_e32 v149, 2, v146
	v_lshlrev_b32_e32 v157, 6, v150
	v_cndmask_b32_e32 v156, v185, v187, vcc
	v_lshlrev_b32_e32 v146, 2, v156
	v_or_b32_e32 v156, v153, v151
	v_add_u32_e32 v152, s18, v156
	v_ashrrev_i32_e32 v153, 31, v152
	v_lshl_or_b32 v182, v150, 10, v204
	v_or3_b32 v150, v157, s16, v158
	v_lshlrev_b64 v[158:159], 13, v[152:153]
	v_ashrrev_i32_e32 v151, 31, v150
	v_lshlrev_b64 v[160:161], 12, v[152:153]
	v_lshl_add_u64 v[158:159], s[2:3], 0, v[158:159]
	v_lshl_add_u64 v[160:161], s[4:5], 0, v[160:161]
	v_lshl_add_u64 v[166:167], v[150:151], 2, v[158:159]
	v_lshl_add_u64 v[168:169], v[150:151], 1, v[160:161]
	s_waitcnt vmcnt(7)
	v_pk_add_f32 v[158:159], v[162:163], v[120:121]
	s_waitcnt vmcnt(6)
	v_pk_add_f32 v[120:121], v[242:243], v[128:129]
	s_waitcnt vmcnt(5)
	v_pk_add_f32 v[128:129], v[238:239], v[136:137]
	s_waitcnt vmcnt(4)
	v_pk_add_f32 v[136:137], v[234:235], v[140:141]
	v_pk_add_f32 v[160:161], v[164:165], v[122:123]
	v_pk_add_f32 v[122:123], v[244:245], v[130:131]
	v_pk_add_f32 v[130:131], v[240:241], v[138:139]
	v_pk_add_f32 v[138:139], v[236:237], v[142:143]
	v_pk_mul_f32 v[172:173], v[128:129], v[128:129]
	v_pk_mul_f32 v[178:179], v[136:137], v[136:137]
	v_pk_mul_f32 v[162:163], v[120:121], v[120:121]
	v_pk_mul_f32 v[174:175], v[130:131], v[130:131]
	v_cvt_pk_bf16_f32 v176, v136, v137
	v_pk_mul_f32 v[180:181], v[138:139], v[138:139]
	global_store_dwordx4 v[166:167], v[136:139], off
	v_add_f32_e32 v153, v172, v173
	v_add_f32_e32 v157, v178, v179
	v_pk_mul_f32 v[136:137], v[158:159], v[158:159]
	v_pk_mul_f32 v[164:165], v[122:123], v[122:123]
	v_cvt_pk_bf16_f32 v177, v138, v139
	v_pk_mul_f32 v[138:139], v[160:161], v[160:161]
	v_add_f32_e32 v162, v162, v163
	v_add_f32_e32 v136, v136, v137
	v_add_f32_e32 v137, v174, v153
	v_add_f32_e32 v153, v180, v157
	v_add_f32_e32 v157, v164, v162
	v_add_f32_e32 v136, v138, v136
	v_add_f32_e32 v137, v175, v137
	v_add_f32_e32 v138, v181, v153
	v_add_f32_e32 v153, v165, v157
	v_add_f32_e32 v137, v138, v137
	v_add_f32_e32 v137, v137, v153
	v_add_f32_e32 v136, v139, v136
	v_add_f32_e32 v136, v137, v136
	ds_bpermute_b32 v137, v149, v136
	v_cvt_pk_bf16_f32 v170, v128, v129
	v_cvt_pk_bf16_f32 v171, v130, v131
	v_cvt_pk_bf16_f32 v142, v120, v121
	global_store_dwordx2 v[168:169], v[176:177], off
	global_store_dwordx4 v[166:167], v[128:131], off offset:64
	global_store_dwordx2 v[168:169], v[170:171], off offset:32
	global_store_dwordx4 v[166:167], v[120:123], off offset:128
	v_cvt_pk_bf16_f32 v140, v158, v159
	v_cvt_pk_bf16_f32 v141, v160, v161
	s_waitcnt lgkmcnt(0)
	v_add_f32_e32 v120, v136, v137
	ds_bpermute_b32 v121, v146, v120
	v_cvt_pk_bf16_f32 v143, v122, v123
	v_lshl_add_u32 v153, v156, 2, v182
	global_store_dwordx2 v[168:169], v[142:143], off offset:64
	global_store_dwordx4 v[166:167], v[158:161], off offset:192
	global_store_dwordx2 v[168:169], v[140:141], off offset:96
	s_and_saveexec_b64 s[16:17], s[0:1]
	s_cbranch_execz .LBB0_156
	s_waitcnt lgkmcnt(0)
	v_add_f32_e32 v120, v120, v121
	ds_write_b32 v153, v120

.LBB0_252:
	s_mul_i32 s16, s19, 0x300000
	s_mul_hi_i32 s17, s19, 0x300000
	s_add_u32 s16, s22, s16
	s_addc_u32 s17, s23, s17
	s_mul_hi_i32 s19, s18, 0x300000
	s_mul_i32 s18, s18, 0x300000
	s_add_u32 s18, s24, s18
	s_addc_u32 s19, s25, s19
	s_add_u32 s44, s0, 0x80
	v_and_b32_e32 v8, 48, v7
	v_lshlrev_b32_e32 v9, 6, v7
	v_lshlrev_b32_e32 v7, 2, v7
	s_addc_u32 s45, s1, 0
	v_and_b32_e32 v10, 0x3c0, v9
	v_and_b32_e32 v149, 32, v7
	s_add_u32 s46, s14, 0x80
	v_or_b32_e32 v145, v10, v8
	v_bitop3_b32 v12, v10, v149, v8 bitop3:0x36
	s_waitcnt vmcnt(0)
	s_barrier
	v_lshlrev_b32_e32 v8, 13, v6
	s_addc_u32 s47, s15, 0
	s_add_i32 s38, s27, 0x10000
	v_lshl_add_u64 v[6:7], s[44:45], 0, v[0:1]
	s_mov_b32 s39, m0
	s_mov_b32 m0, s38
	s_nop 0
	global_load_lds_dwordx4 v[6:7], off
	s_mov_b32 m0, s39
	s_add_i32 s37, s27, 0x18000
	v_lshl_add_u64 v[6:7], s[46:47], 0, v[0:1]
	s_mov_b32 s39, m0
	s_mov_b32 m0, s37
	s_nop 0
	global_load_lds_dwordx4 v[6:7], off
	s_mov_b32 m0, s39
	v_lshl_add_u64 v[6:7], s[44:45], 0, v[2:3]
	s_add_i32 s39, s27, 0x12000
	s_mov_b32 s40, m0
	s_mov_b32 m0, s39
	s_nop 0
	global_load_lds_dwordx4 v[6:7], off
	s_mov_b32 m0, s40
	v_lshl_add_u64 v[6:7], s[46:47], 0, v[2:3]
	s_add_i32 s40, s27, 0x1a000
	s_mov_b32 s41, m0
	s_mov_b32 m0, s40
	s_nop 0
	global_load_lds_dwordx4 v[6:7], off
	s_mov_b32 m0, s41
	v_lshl_add_u64 v[6:7], s[44:45], 0, v[4:5]
	s_add_i32 s41, s27, 0x14000
	s_mov_b32 s42, m0
	s_mov_b32 m0, s41
	s_nop 0
	global_load_lds_dwordx4 v[6:7], off
	s_mov_b32 m0, s42
	v_lshl_add_u64 v[6:7], s[46:47], 0, v[4:5]
	s_add_i32 s42, s27, 0x1c000
	s_mov_b32 s43, m0
	s_mov_b32 m0, s42
	s_nop 0
	global_load_lds_dwordx4 v[6:7], off
	s_mov_b32 m0, s43
	v_lshl_add_u64 v[6:7], s[44:45], 0, v[146:147]
	s_add_i32 s43, s27, 0x16000
	s_mov_b32 s44, m0
	s_mov_b32 m0, s43
	s_nop 0
	global_load_lds_dwordx4 v[6:7], off
	s_mov_b32 m0, s44
	v_lshl_add_u64 v[6:7], s[46:47], 0, v[146:147]
	s_add_i32 s44, s27, 0x1e000
	s_mov_b32 s45, m0
	s_mov_b32 m0, s44
	s_nop 0
	global_load_lds_dwordx4 v[6:7], off
	s_mov_b32 m0, s45
	v_and_b32_e32 v182, 0xffffc000, v9
	v_or_b32_e32 v183, 0x800, v182
	v_or_b32_e32 v189, 0x1000, v182
	v_or_b32_e32 v199, 0x1800, v182
	v_or_b32_e32 v200, 0x2000, v182
	v_or_b32_e32 v201, 0x2800, v182
	v_or_b32_e32 v203, 0x3000, v182
	v_or_b32_e32 v206, 0x3800, v182
	s_movk_i32 s45, 0x6000
	v_and_or_b32 v7, v8, s45, v12
	ds_read_b128 v[8:11], v7 offset:32768
	v_or_b32_e32 v6, v12, v182
	ds_read_b128 v[12:15], v7 offset:34816
	ds_read_b128 v[16:19], v7 offset:36864
	ds_read_b128 v[24:27], v7 offset:38912
	ds_read_b128 v[20:23], v6
	ds_read_b128 v[28:31], v6 offset:2048
	ds_read_b128 v[32:35], v6 offset:4096
	ds_read_b128 v[36:39], v6 offset:6144
	s_waitcnt lgkmcnt(3)
	v_mfma_f32_16x16x32_bf16 v[40:43], v[8:11], v[20:23], 0
	v_mfma_f32_16x16x32_bf16 v[44:47], v[12:15], v[20:23], 0
	v_mfma_f32_16x16x32_bf16 v[48:51], v[16:19], v[20:23], 0
	v_mfma_f32_16x16x32_bf16 v[20:23], v[24:27], v[20:23], 0
	ds_read_b128 v[52:55], v6 offset:8192
	s_waitcnt lgkmcnt(3)
	v_mfma_f32_16x16x32_bf16 v[56:59], v[8:11], v[28:31], 0
	v_mfma_f32_16x16x32_bf16 v[60:63], v[12:15], v[28:31], 0
	v_mfma_f32_16x16x32_bf16 v[64:67], v[16:19], v[28:31], 0
	v_mfma_f32_16x16x32_bf16 v[28:31], v[24:27], v[28:31], 0
	ds_read_b128 v[68:71], v6 offset:10240
	s_waitcnt lgkmcnt(3)
	v_mfma_f32_16x16x32_bf16 v[72:75], v[8:11], v[32:35], 0
	v_mfma_f32_16x16x32_bf16 v[76:79], v[12:15], v[32:35], 0
	v_mfma_f32_16x16x32_bf16 v[80:83], v[16:19], v[32:35], 0
	v_mfma_f32_16x16x32_bf16 v[32:35], v[24:27], v[32:35], 0
	ds_read_b128 v[84:87], v6 offset:12288
	s_waitcnt lgkmcnt(3)
	v_mfma_f32_16x16x32_bf16 v[88:91], v[8:11], v[36:39], 0
	v_mfma_f32_16x16x32_bf16 v[92:95], v[12:15], v[36:39], 0
	v_mfma_f32_16x16x32_bf16 v[96:99], v[16:19], v[36:39], 0
	v_mfma_f32_16x16x32_bf16 v[36:39], v[24:27], v[36:39], 0
	ds_read_b128 v[100:103], v6 offset:14336
	s_waitcnt lgkmcnt(3)
	v_mfma_f32_16x16x32_bf16 v[104:107], v[8:11], v[52:55], 0
	v_mfma_f32_16x16x32_bf16 v[108:111], v[12:15], v[52:55], 0
	v_mfma_f32_16x16x32_bf16 v[112:115], v[16:19], v[52:55], 0
	v_mfma_f32_16x16x32_bf16 v[52:55], v[24:27], v[52:55], 0
	s_waitcnt lgkmcnt(2)
	v_mfma_f32_16x16x32_bf16 v[116:119], v[8:11], v[68:71], 0
	v_mfma_f32_16x16x32_bf16 v[120:123], v[12:15], v[68:71], 0
	v_mfma_f32_16x16x32_bf16 v[124:127], v[16:19], v[68:71], 0
	v_mfma_f32_16x16x32_bf16 v[68:71], v[24:27], v[68:71], 0
	s_waitcnt lgkmcnt(1)
	v_mfma_f32_16x16x32_bf16 v[128:131], v[8:11], v[84:87], 0
	v_mfma_f32_16x16x32_bf16 v[132:135], v[12:15], v[84:87], 0
	v_mfma_f32_16x16x32_bf16 v[136:139], v[16:19], v[84:87], 0
	v_mfma_f32_16x16x32_bf16 v[84:87], v[24:27], v[84:87], 0
	s_waitcnt lgkmcnt(0)
	v_mfma_f32_16x16x32_bf16 v[8:11], v[8:11], v[100:103], 0
	v_mfma_f32_16x16x32_bf16 v[12:15], v[12:15], v[100:103], 0
	v_mfma_f32_16x16x32_bf16 v[16:19], v[16:19], v[100:103], 0
	v_mfma_f32_16x16x32_bf16 v[24:27], v[24:27], v[100:103], 0
	ds_read_b128 v[100:103], v7 offset:33792
	ds_read_b128 v[140:143], v7 offset:35840
	ds_read_b128 v[150:153], v7 offset:37888
	ds_read_b128 v[158:161], v7 offset:39936
	ds_read_b128 v[154:157], v6 offset:1024
	ds_read_b128 v[162:165], v6 offset:3072
	ds_read_b128 v[166:169], v6 offset:5120
	ds_read_b128 v[170:173], v6 offset:7168
	s_waitcnt lgkmcnt(3)
	v_mfma_f32_16x16x32_bf16 v[40:43], v[100:103], v[154:157], v[40:43]
	v_mfma_f32_16x16x32_bf16 v[44:47], v[140:143], v[154:157], v[44:47]
	v_mfma_f32_16x16x32_bf16 v[48:51], v[150:153], v[154:157], v[48:51]
	v_mfma_f32_16x16x32_bf16 v[20:23], v[158:161], v[154:157], v[20:23]
	ds_read_b128 v[154:157], v6 offset:9216
	s_waitcnt lgkmcnt(3)
	v_mfma_f32_16x16x32_bf16 v[56:59], v[100:103], v[162:165], v[56:59]
	v_mfma_f32_16x16x32_bf16 v[60:63], v[140:143], v[162:165], v[60:63]
	v_mfma_f32_16x16x32_bf16 v[64:67], v[150:153], v[162:165], v[64:67]
	v_mfma_f32_16x16x32_bf16 v[28:31], v[158:161], v[162:165], v[28:31]
	ds_read_b128 v[162:165], v6 offset:11264
	s_waitcnt lgkmcnt(3)
	v_mfma_f32_16x16x32_bf16 v[72:75], v[100:103], v[166:169], v[72:75]
	v_mfma_f32_16x16x32_bf16 v[76:79], v[140:143], v[166:169], v[76:79]
	v_mfma_f32_16x16x32_bf16 v[80:83], v[150:153], v[166:169], v[80:83]
	v_mfma_f32_16x16x32_bf16 v[32:35], v[158:161], v[166:169], v[32:35]
	ds_read_b128 v[166:169], v6 offset:13312
	s_waitcnt lgkmcnt(3)
	v_mfma_f32_16x16x32_bf16 v[88:91], v[100:103], v[170:173], v[88:91]
	v_mfma_f32_16x16x32_bf16 v[92:95], v[140:143], v[170:173], v[92:95]
	v_mfma_f32_16x16x32_bf16 v[96:99], v[150:153], v[170:173], v[96:99]
	v_mfma_f32_16x16x32_bf16 v[36:39], v[158:161], v[170:173], v[36:39]
	ds_read_b128 v[170:173], v6 offset:15360
	s_waitcnt lgkmcnt(3)
	v_mfma_f32_16x16x32_bf16 v[104:107], v[100:103], v[154:157], v[104:107]
	v_mfma_f32_16x16x32_bf16 v[108:111], v[140:143], v[154:157], v[108:111]
	v_mfma_f32_16x16x32_bf16 v[112:115], v[150:153], v[154:157], v[112:115]
	v_mfma_f32_16x16x32_bf16 v[52:55], v[158:161], v[154:157], v[52:55]
	s_waitcnt lgkmcnt(2)
	v_mfma_f32_16x16x32_bf16 v[116:119], v[100:103], v[162:165], v[116:119]
	v_mfma_f32_16x16x32_bf16 v[120:123], v[140:143], v[162:165], v[120:123]
	v_mfma_f32_16x16x32_bf16 v[124:127], v[150:153], v[162:165], v[124:127]
	v_mfma_f32_16x16x32_bf16 v[68:71], v[158:161], v[162:165], v[68:71]
	s_waitcnt lgkmcnt(1)
	v_mfma_f32_16x16x32_bf16 v[128:131], v[100:103], v[166:169], v[128:131]
	v_mfma_f32_16x16x32_bf16 v[132:135], v[140:143], v[166:169], v[132:135]
	v_mfma_f32_16x16x32_bf16 v[136:139], v[150:153], v[166:169], v[136:139]
	v_mfma_f32_16x16x32_bf16 v[84:87], v[158:161], v[166:169], v[84:87]
	s_waitcnt lgkmcnt(0)
	v_mfma_f32_16x16x32_bf16 v[100:103], v[100:103], v[170:173], v[8:11]
	v_mfma_f32_16x16x32_bf16 v[150:153], v[150:153], v[170:173], v[16:19]
	v_mfma_f32_16x16x32_bf16 v[24:27], v[158:161], v[170:173], v[24:27]
	v_mfma_f32_16x16x32_bf16 v[140:143], v[140:143], v[170:173], v[12:15]
	s_add_u32 s46, s0, 0x100
	s_addc_u32 s47, s1, 0
	s_add_u32 s48, s14, 0x100
	s_waitcnt vmcnt(0)
	s_barrier
	s_addc_u32 s49, s15, 0
	v_lshl_add_u64 v[8:9], s[46:47], 0, v[0:1]
	s_mov_b32 s45, m0
	s_mov_b32 m0, s27
	s_nop 0
	global_load_lds_dwordx4 v[8:9], off
	s_mov_b32 m0, s45
	v_lshl_add_u64 v[8:9], s[48:49], 0, v[0:1]
	s_mov_b32 s45, m0
	s_mov_b32 m0, s28
	s_nop 0
	global_load_lds_dwordx4 v[8:9], off
	s_mov_b32 m0, s45
	v_lshl_add_u64 v[8:9], s[46:47], 0, v[2:3]
	s_mov_b32 s45, m0
	s_mov_b32 m0, s29
	s_nop 0
	global_load_lds_dwordx4 v[8:9], off
	s_mov_b32 m0, s45
	v_lshl_add_u64 v[8:9], s[48:49], 0, v[2:3]
	s_mov_b32 s45, m0
	s_mov_b32 m0, s30
	s_nop 0
	global_load_lds_dwordx4 v[8:9], off
	s_mov_b32 m0, s45
	v_lshl_add_u64 v[8:9], s[46:47], 0, v[4:5]
	s_mov_b32 s45, m0
	s_mov_b32 m0, s31
	s_nop 0
	global_load_lds_dwordx4 v[8:9], off
	s_mov_b32 m0, s45
	v_lshl_add_u64 v[8:9], s[48:49], 0, v[4:5]
	s_mov_b32 s45, m0
	s_mov_b32 m0, s34
	s_nop 0
	global_load_lds_dwordx4 v[8:9], off
	s_mov_b32 m0, s45
	v_lshl_add_u64 v[8:9], s[46:47], 0, v[146:147]
	s_mov_b32 s45, m0
	s_mov_b32 m0, s35
	s_nop 0
	global_load_lds_dwordx4 v[8:9], off
	s_mov_b32 m0, s45
	v_lshl_add_u64 v[8:9], s[48:49], 0, v[146:147]
	s_mov_b32 s45, m0
	s_mov_b32 m0, s36
	s_nop 0
	global_load_lds_dwordx4 v[8:9], off
	s_mov_b32 m0, s45
	v_or_b32_e32 v8, 0x18000, v7
	v_or_b32_e32 v9, 0x18800, v7
	v_or_b32_e32 v11, 0x19000, v7
	v_or_b32_e32 v10, 0x19800, v7
	ds_read_b128 v[154:157], v8
	ds_read_b128 v[158:161], v9
	ds_read_b128 v[162:165], v11
	ds_read_b128 v[166:169], v10
	v_bitop3_b32 v207, v145, s33, v149 bitop3:0xde
	v_add_u32_e32 v12, v207, v182
	ds_read_b128 v[16:19], v12
	v_add_u32_e32 v13, v207, v183
	v_add_u32_e32 v14, v207, v189
	v_add_u32_e32 v15, v207, v199
	ds_read_b128 v[170:173], v13
	ds_read_b128 v[174:177], v14
	ds_read_b128 v[178:181], v15
	s_waitcnt lgkmcnt(3)
	v_mfma_f32_16x16x32_bf16 v[40:43], v[154:157], v[16:19], v[40:43]
	v_mfma_f32_16x16x32_bf16 v[44:47], v[158:161], v[16:19], v[44:47]
	v_mfma_f32_16x16x32_bf16 v[48:51], v[162:165], v[16:19], v[48:51]
	v_mfma_f32_16x16x32_bf16 v[214:217], v[166:169], v[16:19], v[20:23]
	v_add_u32_e32 v16, v207, v200
	v_add_u32_e32 v17, v207, v201
	v_add_u32_e32 v18, v207, v203
	v_add_u32_e32 v19, v207, v206
	ds_read_b128 v[20:23], v16
	s_waitcnt lgkmcnt(3)
	v_mfma_f32_16x16x32_bf16 v[56:59], v[154:157], v[170:173], v[56:59]
	v_mfma_f32_16x16x32_bf16 v[60:63], v[158:161], v[170:173], v[60:63]
	v_mfma_f32_16x16x32_bf16 v[64:67], v[162:165], v[170:173], v[64:67]
	v_mfma_f32_16x16x32_bf16 v[170:173], v[166:169], v[170:173], v[28:31]
	s_nop 2
	ds_read_b128 v[28:31], v17
	s_waitcnt lgkmcnt(3)
	v_mfma_f32_16x16x32_bf16 v[72:75], v[154:157], v[174:177], v[72:75]
	v_mfma_f32_16x16x32_bf16 v[76:79], v[158:161], v[174:177], v[76:79]
	v_mfma_f32_16x16x32_bf16 v[80:83], v[162:165], v[174:177], v[80:83]
	v_mfma_f32_16x16x32_bf16 v[32:35], v[166:169], v[174:177], v[32:35]
	ds_read_b128 v[174:177], v18
	s_waitcnt lgkmcnt(3)
	v_mfma_f32_16x16x32_bf16 v[88:91], v[154:157], v[178:181], v[88:91]
	v_mfma_f32_16x16x32_bf16 v[92:95], v[158:161], v[178:181], v[92:95]
	v_mfma_f32_16x16x32_bf16 v[96:99], v[162:165], v[178:181], v[96:99]
	v_mfma_f32_16x16x32_bf16 v[36:39], v[166:169], v[178:181], v[36:39]
	ds_read_b128 v[178:181], v19
	s_waitcnt lgkmcnt(3)
	v_mfma_f32_16x16x32_bf16 v[104:107], v[154:157], v[20:23], v[104:107]
	v_mfma_f32_16x16x32_bf16 v[108:111], v[158:161], v[20:23], v[108:111]
	v_mfma_f32_16x16x32_bf16 v[112:115], v[162:165], v[20:23], v[112:115]
	v_mfma_f32_16x16x32_bf16 v[52:55], v[166:169], v[20:23], v[52:55]
	s_waitcnt lgkmcnt(2)
	v_mfma_f32_16x16x32_bf16 v[116:119], v[154:157], v[28:31], v[116:119]
	v_mfma_f32_16x16x32_bf16 v[120:123], v[158:161], v[28:31], v[120:123]
	v_mfma_f32_16x16x32_bf16 v[124:127], v[162:165], v[28:31], v[124:127]
	v_mfma_f32_16x16x32_bf16 v[68:71], v[166:169], v[28:31], v[68:71]
	s_waitcnt lgkmcnt(1)
	v_mfma_f32_16x16x32_bf16 v[128:131], v[154:157], v[174:177], v[128:131]
	v_mfma_f32_16x16x32_bf16 v[132:135], v[158:161], v[174:177], v[132:135]
	v_mfma_f32_16x16x32_bf16 v[84:87], v[166:169], v[174:177], v[84:87]
	s_waitcnt lgkmcnt(0)
	v_mfma_f32_16x16x32_bf16 v[100:103], v[154:157], v[178:181], v[100:103]
	v_mfma_f32_16x16x32_bf16 v[150:153], v[162:165], v[178:181], v[150:153]
	v_mfma_f32_16x16x32_bf16 v[154:157], v[166:169], v[178:181], v[24:27]
	v_mfma_f32_16x16x32_bf16 v[136:139], v[162:165], v[174:177], v[136:139]
	v_mfma_f32_16x16x32_bf16 v[140:143], v[158:161], v[178:181], v[140:143]
	v_or_b32_e32 v20, 0x18400, v7
	v_or_b32_e32 v21, 0x18c00, v7
	v_or_b32_e32 v23, 0x19400, v7
	v_or_b32_e32 v22, 0x19c00, v7
	ds_read_b128 v[158:161], v20
	ds_read_b128 v[162:165], v21
	ds_read_b128 v[166:169], v23
	ds_read_b128 v[174:177], v22
	s_mov_b32 s45, 0x10400
	v_bitop3_b32 v145, v145, s45, v149 bitop3:0xde
	v_add_u32_e32 v24, v145, v182
	ds_read_b128 v[28:31], v24
	v_add_u32_e32 v25, v145, v183
	v_add_u32_e32 v26, v145, v189
	v_add_u32_e32 v27, v145, v199
	ds_read_b128 v[178:181], v25
	ds_read_b128 v[218:221], v26
	ds_read_b128 v[222:225], v27
	s_waitcnt lgkmcnt(3)
	v_mfma_f32_16x16x32_bf16 v[40:43], v[158:161], v[28:31], v[40:43]
	v_mfma_f32_16x16x32_bf16 v[44:47], v[162:165], v[28:31], v[44:47]
	v_mfma_f32_16x16x32_bf16 v[48:51], v[166:169], v[28:31], v[48:51]
	v_mfma_f32_16x16x32_bf16 v[214:217], v[174:177], v[28:31], v[214:217]
	v_add_u32_e32 v28, v145, v200
	v_add_u32_e32 v29, v145, v201
	v_add_u32_e32 v30, v145, v203
	v_add_u32_e32 v31, v145, v206
	ds_read_b128 v[226:229], v28
	s_waitcnt lgkmcnt(3)
	v_mfma_f32_16x16x32_bf16 v[56:59], v[158:161], v[178:181], v[56:59]
	v_mfma_f32_16x16x32_bf16 v[60:63], v[162:165], v[178:181], v[60:63]
	v_mfma_f32_16x16x32_bf16 v[64:67], v[166:169], v[178:181], v[64:67]
	v_mfma_f32_16x16x32_bf16 v[170:173], v[174:177], v[178:181], v[170:173]
	ds_read_b128 v[178:181], v29
	s_waitcnt lgkmcnt(3)
	v_mfma_f32_16x16x32_bf16 v[72:75], v[158:161], v[218:221], v[72:75]
	v_mfma_f32_16x16x32_bf16 v[76:79], v[162:165], v[218:221], v[76:79]
	v_mfma_f32_16x16x32_bf16 v[80:83], v[166:169], v[218:221], v[80:83]
	v_mfma_f32_16x16x32_bf16 v[32:35], v[174:177], v[218:221], v[32:35]
	ds_read_b128 v[218:221], v30
	s_waitcnt lgkmcnt(3)
	v_mfma_f32_16x16x32_bf16 v[88:91], v[158:161], v[222:225], v[88:91]
	v_mfma_f32_16x16x32_bf16 v[92:95], v[162:165], v[222:225], v[92:95]
	v_mfma_f32_16x16x32_bf16 v[96:99], v[166:169], v[222:225], v[96:99]
	v_mfma_f32_16x16x32_bf16 v[36:39], v[174:177], v[222:225], v[36:39]
	ds_read_b128 v[222:225], v31
	s_waitcnt lgkmcnt(3)
	v_mfma_f32_16x16x32_bf16 v[104:107], v[158:161], v[226:229], v[104:107]
	v_mfma_f32_16x16x32_bf16 v[108:111], v[162:165], v[226:229], v[108:111]
	v_mfma_f32_16x16x32_bf16 v[112:115], v[166:169], v[226:229], v[112:115]
	v_mfma_f32_16x16x32_bf16 v[52:55], v[174:177], v[226:229], v[52:55]
	s_waitcnt lgkmcnt(2)
	v_mfma_f32_16x16x32_bf16 v[116:119], v[158:161], v[178:181], v[116:119]
	v_mfma_f32_16x16x32_bf16 v[120:123], v[162:165], v[178:181], v[120:123]
	v_mfma_f32_16x16x32_bf16 v[124:127], v[166:169], v[178:181], v[124:127]
	v_mfma_f32_16x16x32_bf16 v[68:71], v[174:177], v[178:181], v[68:71]
	s_waitcnt lgkmcnt(1)
	v_mfma_f32_16x16x32_bf16 v[132:135], v[162:165], v[218:221], v[132:135]
	v_mfma_f32_16x16x32_bf16 v[84:87], v[174:177], v[218:221], v[84:87]
	s_waitcnt lgkmcnt(0)
	v_mfma_f32_16x16x32_bf16 v[100:103], v[158:161], v[222:225], v[100:103]
	v_mfma_f32_16x16x32_bf16 v[150:153], v[166:169], v[222:225], v[150:153]
	v_mfma_f32_16x16x32_bf16 v[154:157], v[174:177], v[222:225], v[154:157]
	v_mfma_f32_16x16x32_bf16 v[128:131], v[158:161], v[218:221], v[128:131]
	v_mfma_f32_16x16x32_bf16 v[136:139], v[166:169], v[218:221], v[136:139]
	v_mfma_f32_16x16x32_bf16 v[140:143], v[162:165], v[222:225], v[140:143]
	s_add_u32 s46, s0, 0x180
	s_addc_u32 s47, s1, 0
	s_add_u32 s48, s14, 0x180
	s_waitcnt vmcnt(0)
	s_barrier
	s_addc_u32 s49, s15, 0
	v_lshl_add_u64 v[158:159], s[46:47], 0, v[0:1]
	s_mov_b32 s45, m0
	s_mov_b32 m0, s38
	s_nop 0
	global_load_lds_dwordx4 v[158:159], off
	s_mov_b32 m0, s45
	v_lshl_add_u64 v[158:159], s[48:49], 0, v[0:1]
	s_mov_b32 s45, m0
	s_mov_b32 m0, s37
	s_nop 0
	global_load_lds_dwordx4 v[158:159], off
	s_mov_b32 m0, s45
	v_lshl_add_u64 v[158:159], s[46:47], 0, v[2:3]
	s_mov_b32 s45, m0
	s_mov_b32 m0, s39
	s_nop 0
	global_load_lds_dwordx4 v[158:159], off
	s_mov_b32 m0, s45
	v_lshl_add_u64 v[158:159], s[48:49], 0, v[2:3]
	s_mov_b32 s45, m0
	s_mov_b32 m0, s40
	s_nop 0
	global_load_lds_dwordx4 v[158:159], off
	s_mov_b32 m0, s45
	v_lshl_add_u64 v[158:159], s[46:47], 0, v[4:5]
	s_mov_b32 s45, m0
	s_mov_b32 m0, s41
	s_nop 0
	global_load_lds_dwordx4 v[158:159], off
	s_mov_b32 m0, s45
	v_lshl_add_u64 v[158:159], s[48:49], 0, v[4:5]
	s_mov_b32 s45, m0
	s_mov_b32 m0, s42
	s_nop 0
	global_load_lds_dwordx4 v[158:159], off
	s_mov_b32 m0, s45
	v_lshl_add_u64 v[158:159], s[46:47], 0, v[146:147]
	s_mov_b32 s45, m0
	s_mov_b32 m0, s43
	s_nop 0
	global_load_lds_dwordx4 v[158:159], off
	s_mov_b32 m0, s45
	v_lshl_add_u64 v[158:159], s[48:49], 0, v[146:147]
	s_mov_b32 s45, m0
	s_mov_b32 m0, s44
	s_nop 0
	global_load_lds_dwordx4 v[158:159], off
	s_mov_b32 m0, s45
	ds_read_b128 v[158:161], v7 offset:32768
	ds_read_b128 v[162:165], v7 offset:34816
	ds_read_b128 v[166:169], v7 offset:36864
	ds_read_b128 v[178:181], v7 offset:38912
	ds_read_b128 v[174:177], v6
	ds_read_b128 v[218:221], v6 offset:2048
	ds_read_b128 v[222:225], v6 offset:4096
	ds_read_b128 v[226:229], v6 offset:6144
	s_waitcnt lgkmcnt(3)
	v_mfma_f32_16x16x32_bf16 v[40:43], v[158:161], v[174:177], v[40:43]
	v_mfma_f32_16x16x32_bf16 v[44:47], v[162:165], v[174:177], v[44:47]
	v_mfma_f32_16x16x32_bf16 v[48:51], v[166:169], v[174:177], v[48:51]
	v_mfma_f32_16x16x32_bf16 v[174:177], v[178:181], v[174:177], v[214:217]
	s_nop 2
	ds_read_b128 v[214:217], v6 offset:8192
	s_waitcnt lgkmcnt(3)
	v_mfma_f32_16x16x32_bf16 v[56:59], v[158:161], v[218:221], v[56:59]
	v_mfma_f32_16x16x32_bf16 v[60:63], v[162:165], v[218:221], v[60:63]
	v_mfma_f32_16x16x32_bf16 v[64:67], v[166:169], v[218:221], v[64:67]
	v_mfma_f32_16x16x32_bf16 v[170:173], v[178:181], v[218:221], v[170:173]
	ds_read_b128 v[218:221], v6 offset:10240
	s_waitcnt lgkmcnt(3)
	v_mfma_f32_16x16x32_bf16 v[72:75], v[158:161], v[222:225], v[72:75]
	v_mfma_f32_16x16x32_bf16 v[76:79], v[162:165], v[222:225], v[76:79]
	v_mfma_f32_16x16x32_bf16 v[80:83], v[166:169], v[222:225], v[80:83]
	v_mfma_f32_16x16x32_bf16 v[32:35], v[178:181], v[222:225], v[32:35]
	ds_read_b128 v[222:225], v6 offset:12288
	s_waitcnt lgkmcnt(3)
	v_mfma_f32_16x16x32_bf16 v[88:91], v[158:161], v[226:229], v[88:91]
	v_mfma_f32_16x16x32_bf16 v[92:95], v[162:165], v[226:229], v[92:95]
	v_mfma_f32_16x16x32_bf16 v[96:99], v[166:169], v[226:229], v[96:99]
	v_mfma_f32_16x16x32_bf16 v[36:39], v[178:181], v[226:229], v[36:39]
	ds_read_b128 v[226:229], v6 offset:14336
	s_waitcnt lgkmcnt(3)
	v_mfma_f32_16x16x32_bf16 v[104:107], v[158:161], v[214:217], v[104:107]
	v_mfma_f32_16x16x32_bf16 v[108:111], v[162:165], v[214:217], v[108:111]
	v_mfma_f32_16x16x32_bf16 v[112:115], v[166:169], v[214:217], v[112:115]
	v_mfma_f32_16x16x32_bf16 v[52:55], v[178:181], v[214:217], v[52:55]
	s_waitcnt lgkmcnt(2)
	v_mfma_f32_16x16x32_bf16 v[116:119], v[158:161], v[218:221], v[116:119]
	v_mfma_f32_16x16x32_bf16 v[120:123], v[162:165], v[218:221], v[120:123]
	v_mfma_f32_16x16x32_bf16 v[124:127], v[166:169], v[218:221], v[124:127]
	v_mfma_f32_16x16x32_bf16 v[68:71], v[178:181], v[218:221], v[68:71]
	s_waitcnt lgkmcnt(1)
	v_mfma_f32_16x16x32_bf16 v[132:135], v[162:165], v[222:225], v[132:135]
	v_mfma_f32_16x16x32_bf16 v[84:87], v[178:181], v[222:225], v[84:87]
	s_waitcnt lgkmcnt(0)
	v_mfma_f32_16x16x32_bf16 v[100:103], v[158:161], v[226:229], v[100:103]
	v_mfma_f32_16x16x32_bf16 v[150:153], v[166:169], v[226:229], v[150:153]
	v_mfma_f32_16x16x32_bf16 v[154:157], v[178:181], v[226:229], v[154:157]
	v_mfma_f32_16x16x32_bf16 v[128:131], v[158:161], v[222:225], v[128:131]
	v_mfma_f32_16x16x32_bf16 v[136:139], v[166:169], v[222:225], v[136:139]
	v_mfma_f32_16x16x32_bf16 v[140:143], v[162:165], v[226:229], v[140:143]
	ds_read_b128 v[158:161], v7 offset:33792
	ds_read_b128 v[162:165], v7 offset:35840
	ds_read_b128 v[166:169], v7 offset:37888
	ds_read_b128 v[214:217], v7 offset:39936
	ds_read_b128 v[178:181], v6 offset:1024
	ds_read_b128 v[218:221], v6 offset:3072
	ds_read_b128 v[222:225], v6 offset:5120
	ds_read_b128 v[226:229], v6 offset:7168
	s_waitcnt lgkmcnt(3)
	v_mfma_f32_16x16x32_bf16 v[40:43], v[158:161], v[178:181], v[40:43]
	v_mfma_f32_16x16x32_bf16 v[44:47], v[162:165], v[178:181], v[44:47]
	v_mfma_f32_16x16x32_bf16 v[48:51], v[166:169], v[178:181], v[48:51]
	v_mfma_f32_16x16x32_bf16 v[174:177], v[214:217], v[178:181], v[174:177]
	ds_read_b128 v[178:181], v6 offset:9216
	s_waitcnt lgkmcnt(3)
	v_mfma_f32_16x16x32_bf16 v[56:59], v[158:161], v[218:221], v[56:59]
	v_mfma_f32_16x16x32_bf16 v[60:63], v[162:165], v[218:221], v[60:63]
	v_mfma_f32_16x16x32_bf16 v[64:67], v[166:169], v[218:221], v[64:67]
	v_mfma_f32_16x16x32_bf16 v[170:173], v[214:217], v[218:221], v[170:173]
	ds_read_b128 v[218:221], v6 offset:11264
	s_waitcnt lgkmcnt(3)
	v_mfma_f32_16x16x32_bf16 v[72:75], v[158:161], v[222:225], v[72:75]
	v_mfma_f32_16x16x32_bf16 v[76:79], v[162:165], v[222:225], v[76:79]
	v_mfma_f32_16x16x32_bf16 v[80:83], v[166:169], v[222:225], v[80:83]
	v_mfma_f32_16x16x32_bf16 v[32:35], v[214:217], v[222:225], v[32:35]
	ds_read_b128 v[222:225], v6 offset:13312
	s_waitcnt lgkmcnt(3)
	v_mfma_f32_16x16x32_bf16 v[88:91], v[158:161], v[226:229], v[88:91]
	v_mfma_f32_16x16x32_bf16 v[92:95], v[162:165], v[226:229], v[92:95]
	v_mfma_f32_16x16x32_bf16 v[96:99], v[166:169], v[226:229], v[96:99]
	v_mfma_f32_16x16x32_bf16 v[36:39], v[214:217], v[226:229], v[36:39]
	ds_read_b128 v[226:229], v6 offset:15360
	s_waitcnt lgkmcnt(3)
	v_mfma_f32_16x16x32_bf16 v[104:107], v[158:161], v[178:181], v[104:107]
	v_mfma_f32_16x16x32_bf16 v[108:111], v[162:165], v[178:181], v[108:111]
	v_mfma_f32_16x16x32_bf16 v[112:115], v[166:169], v[178:181], v[112:115]
	v_mfma_f32_16x16x32_bf16 v[52:55], v[214:217], v[178:181], v[52:55]
	s_waitcnt lgkmcnt(2)
	v_mfma_f32_16x16x32_bf16 v[116:119], v[158:161], v[218:221], v[116:119]
	v_mfma_f32_16x16x32_bf16 v[120:123], v[162:165], v[218:221], v[120:123]
	v_mfma_f32_16x16x32_bf16 v[124:127], v[166:169], v[218:221], v[124:127]
	v_mfma_f32_16x16x32_bf16 v[68:71], v[214:217], v[218:221], v[68:71]
	s_waitcnt lgkmcnt(1)
	v_mfma_f32_16x16x32_bf16 v[132:135], v[162:165], v[222:225], v[132:135]
	v_mfma_f32_16x16x32_bf16 v[84:87], v[214:217], v[222:225], v[84:87]
	s_waitcnt lgkmcnt(0)
	v_mfma_f32_16x16x32_bf16 v[100:103], v[158:161], v[226:229], v[100:103]
	v_mfma_f32_16x16x32_bf16 v[150:153], v[166:169], v[226:229], v[150:153]
	v_mfma_f32_16x16x32_bf16 v[154:157], v[214:217], v[226:229], v[154:157]
	v_mfma_f32_16x16x32_bf16 v[128:131], v[158:161], v[222:225], v[128:131]
	v_mfma_f32_16x16x32_bf16 v[136:139], v[166:169], v[222:225], v[136:139]
	v_mfma_f32_16x16x32_bf16 v[140:143], v[162:165], v[226:229], v[140:143]
	s_add_u32 s46, s0, 0x200
	s_addc_u32 s47, s1, 0
	s_add_u32 s48, s14, 0x200
	s_waitcnt vmcnt(0)
	s_barrier
	s_addc_u32 s49, s15, 0
	ds_read_b128 v[158:161], v8
	ds_read_b128 v[162:165], v12
	ds_read_b128 v[166:169], v9
	ds_read_b128 v[178:181], v13
	ds_read_b128 v[214:217], v11
	ds_read_b128 v[218:221], v10
	ds_read_b128 v[222:225], v14
	ds_read_b128 v[226:229], v15
	s_waitcnt lgkmcnt(6)
	v_mfma_f32_16x16x32_bf16 v[40:43], v[158:161], v[162:165], v[40:43]
	s_waitcnt lgkmcnt(5)
	v_mfma_f32_16x16x32_bf16 v[44:47], v[166:169], v[162:165], v[44:47]
	s_waitcnt lgkmcnt(4)
	v_mfma_f32_16x16x32_bf16 v[56:59], v[158:161], v[178:181], v[56:59]
	s_mov_b32 m0, s27
	v_mfma_f32_16x16x32_bf16 v[60:63], v[166:169], v[178:181], v[60:63]
	global_load_lds_dwordx4 v0, s[46:47]
	s_waitcnt lgkmcnt(3)
	v_mfma_f32_16x16x32_bf16 v[48:51], v[214:217], v[162:165], v[48:51]
	v_mfma_f32_16x16x32_bf16 v[64:67], v[214:217], v[178:181], v[64:67]
	s_waitcnt lgkmcnt(2)
	v_mfma_f32_16x16x32_bf16 v[174:177], v[218:221], v[162:165], v[174:177]
	ds_read_b128 v[162:165], v16
	v_mfma_f32_16x16x32_bf16 v[170:173], v[218:221], v[178:181], v[170:173]
	ds_read_b128 v[178:181], v17
	s_waitcnt lgkmcnt(3)
	s_mov_b32 m0, s28
	v_mfma_f32_16x16x32_bf16 v[72:75], v[158:161], v[222:225], v[72:75]
	global_load_lds_dwordx4 v0, s[48:49]
	v_mfma_f32_16x16x32_bf16 v[76:79], v[166:169], v[222:225], v[76:79]
	v_mfma_f32_16x16x32_bf16 v[80:83], v[214:217], v[222:225], v[80:83]
	v_mfma_f32_16x16x32_bf16 v[32:35], v[218:221], v[222:225], v[32:35]
	ds_read_b128 v[222:225], v18
	s_waitcnt lgkmcnt(3)
	v_mfma_f32_16x16x32_bf16 v[88:91], v[158:161], v[226:229], v[88:91]
	s_mov_b32 m0, s29
	v_mfma_f32_16x16x32_bf16 v[92:95], v[166:169], v[226:229], v[92:95]
	global_load_lds_dwordx4 v2, s[46:47]
	v_mfma_f32_16x16x32_bf16 v[96:99], v[214:217], v[226:229], v[96:99]
	v_mfma_f32_16x16x32_bf16 v[36:39], v[218:221], v[226:229], v[36:39]
	ds_read_b128 v[226:229], v19
	s_waitcnt lgkmcnt(3)
	v_mfma_f32_16x16x32_bf16 v[104:107], v[158:161], v[162:165], v[104:107]
	s_waitcnt lgkmcnt(2)
	v_mfma_f32_16x16x32_bf16 v[116:119], v[158:161], v[178:181], v[116:119]
	s_waitcnt lgkmcnt(1)
	s_mov_b32 m0, s30
	v_mfma_f32_16x16x32_bf16 v[128:131], v[158:161], v[222:225], v[128:131]
	global_load_lds_dwordx4 v2, s[48:49]
	s_waitcnt lgkmcnt(0)
	v_mfma_f32_16x16x32_bf16 v[100:103], v[158:161], v[226:229], v[100:103]
	ds_read_b128 v[158:161], v20
	v_mfma_f32_16x16x32_bf16 v[108:111], v[166:169], v[162:165], v[108:111]
	v_mfma_f32_16x16x32_bf16 v[120:123], v[166:169], v[178:181], v[120:123]
	v_mfma_f32_16x16x32_bf16 v[132:135], v[166:169], v[222:225], v[132:135]
	s_mov_b32 m0, s31
	v_mfma_f32_16x16x32_bf16 v[140:143], v[166:169], v[226:229], v[140:143]
	global_load_lds_dwordx4 v4, s[46:47]
	ds_read_b128 v[166:169], v24
	v_mfma_f32_16x16x32_bf16 v[112:115], v[214:217], v[162:165], v[112:115]
	v_mfma_f32_16x16x32_bf16 v[52:55], v[218:221], v[162:165], v[52:55]
	ds_read_b128 v[162:165], v21
	v_mfma_f32_16x16x32_bf16 v[124:127], v[214:217], v[178:181], v[124:127]
	v_mfma_f32_16x16x32_bf16 v[68:71], v[218:221], v[178:181], v[68:71]
	ds_read_b128 v[178:181], v25
	s_mov_b32 m0, s34
	v_mfma_f32_16x16x32_bf16 v[136:139], v[214:217], v[222:225], v[136:139]
	global_load_lds_dwordx4 v4, s[48:49]
	v_mfma_f32_16x16x32_bf16 v[84:87], v[218:221], v[222:225], v[84:87]
	ds_read_b128 v[222:225], v26
	v_mfma_f32_16x16x32_bf16 v[150:153], v[214:217], v[226:229], v[150:153]
	ds_read_b128 v[214:217], v23
	v_mfma_f32_16x16x32_bf16 v[154:157], v[218:221], v[226:229], v[154:157]
	ds_read_b128 v[218:221], v22
	ds_read_b128 v[226:229], v27
	s_waitcnt lgkmcnt(6)
	v_mfma_f32_16x16x32_bf16 v[40:43], v[158:161], v[166:169], v[40:43]
	s_waitcnt lgkmcnt(5)
	s_mov_b32 m0, s35
	v_mfma_f32_16x16x32_bf16 v[44:47], v[162:165], v[166:169], v[44:47]
	global_load_lds_dwordx4 v146, s[46:47]
	s_waitcnt lgkmcnt(4)
	v_mfma_f32_16x16x32_bf16 v[56:59], v[158:161], v[178:181], v[56:59]
	v_mfma_f32_16x16x32_bf16 v[60:63], v[162:165], v[178:181], v[60:63]
	s_waitcnt lgkmcnt(3)
	v_mfma_f32_16x16x32_bf16 v[72:75], v[158:161], v[222:225], v[72:75]
	v_mfma_f32_16x16x32_bf16 v[76:79], v[162:165], v[222:225], v[76:79]
	s_waitcnt lgkmcnt(2)
	s_mov_b32 m0, s36
	v_mfma_f32_16x16x32_bf16 v[48:51], v[214:217], v[166:169], v[48:51]
	global_load_lds_dwordx4 v146, s[48:49]
	s_waitcnt lgkmcnt(1)
	v_mfma_f32_16x16x32_bf16 v[174:177], v[218:221], v[166:169], v[174:177]
	ds_read_b128 v[166:169], v28
	v_mfma_f32_16x16x32_bf16 v[64:67], v[214:217], v[178:181], v[64:67]
	v_mfma_f32_16x16x32_bf16 v[170:173], v[218:221], v[178:181], v[170:173]
	ds_read_b128 v[178:181], v29
	v_mfma_f32_16x16x32_bf16 v[80:83], v[214:217], v[222:225], v[80:83]
	v_mfma_f32_16x16x32_bf16 v[32:35], v[218:221], v[222:225], v[32:35]
	ds_read_b128 v[222:225], v30
	s_waitcnt lgkmcnt(3)
	v_mfma_f32_16x16x32_bf16 v[88:91], v[158:161], v[226:229], v[88:91]
	v_mfma_f32_16x16x32_bf16 v[92:95], v[162:165], v[226:229], v[92:95]
	v_mfma_f32_16x16x32_bf16 v[96:99], v[214:217], v[226:229], v[96:99]
	v_mfma_f32_16x16x32_bf16 v[36:39], v[218:221], v[226:229], v[36:39]
	ds_read_b128 v[226:229], v31
	s_waitcnt lgkmcnt(3)
	v_mfma_f32_16x16x32_bf16 v[104:107], v[158:161], v[166:169], v[104:107]
	v_mfma_f32_16x16x32_bf16 v[108:111], v[162:165], v[166:169], v[108:111]
	v_mfma_f32_16x16x32_bf16 v[112:115], v[214:217], v[166:169], v[112:115]
	v_mfma_f32_16x16x32_bf16 v[52:55], v[218:221], v[166:169], v[52:55]
	s_waitcnt lgkmcnt(2)
	v_mfma_f32_16x16x32_bf16 v[116:119], v[158:161], v[178:181], v[116:119]
	v_mfma_f32_16x16x32_bf16 v[120:123], v[162:165], v[178:181], v[120:123]
	v_mfma_f32_16x16x32_bf16 v[124:127], v[214:217], v[178:181], v[124:127]
	v_mfma_f32_16x16x32_bf16 v[68:71], v[218:221], v[178:181], v[68:71]
	s_waitcnt lgkmcnt(1)
	v_mfma_f32_16x16x32_bf16 v[128:131], v[158:161], v[222:225], v[128:131]
	v_mfma_f32_16x16x32_bf16 v[132:135], v[162:165], v[222:225], v[132:135]
	v_mfma_f32_16x16x32_bf16 v[136:139], v[214:217], v[222:225], v[136:139]
	v_mfma_f32_16x16x32_bf16 v[84:87], v[218:221], v[222:225], v[84:87]
	s_waitcnt lgkmcnt(0)
	v_mfma_f32_16x16x32_bf16 v[100:103], v[158:161], v[226:229], v[100:103]
	v_mfma_f32_16x16x32_bf16 v[140:143], v[162:165], v[226:229], v[140:143]
	v_mfma_f32_16x16x32_bf16 v[150:153], v[214:217], v[226:229], v[150:153]
	v_mfma_f32_16x16x32_bf16 v[154:157], v[218:221], v[226:229], v[154:157]
	s_add_u32 s46, s0, 0x280
	s_addc_u32 s47, s1, 0
	s_add_u32 s48, s14, 0x280
	s_waitcnt vmcnt(0)
	s_barrier
	s_addc_u32 s49, s15, 0
	ds_read_b128 v[158:161], v7 offset:32768
	ds_read_b128 v[162:165], v6
	ds_read_b128 v[166:169], v7 offset:34816
	ds_read_b128 v[178:181], v6 offset:2048
	ds_read_b128 v[214:217], v7 offset:36864
	ds_read_b128 v[218:221], v7 offset:38912
	ds_read_b128 v[222:225], v6 offset:4096
	ds_read_b128 v[226:229], v6 offset:6144
	s_waitcnt lgkmcnt(6)
	v_mfma_f32_16x16x32_bf16 v[40:43], v[158:161], v[162:165], v[40:43]
	s_waitcnt lgkmcnt(5)
	v_mfma_f32_16x16x32_bf16 v[44:47], v[166:169], v[162:165], v[44:47]
	s_waitcnt lgkmcnt(4)
	v_mfma_f32_16x16x32_bf16 v[56:59], v[158:161], v[178:181], v[56:59]
	s_mov_b32 m0, s38
	v_mfma_f32_16x16x32_bf16 v[60:63], v[166:169], v[178:181], v[60:63]
	global_load_lds_dwordx4 v0, s[46:47]
	s_waitcnt lgkmcnt(3)
	v_mfma_f32_16x16x32_bf16 v[48:51], v[214:217], v[162:165], v[48:51]
	v_mfma_f32_16x16x32_bf16 v[64:67], v[214:217], v[178:181], v[64:67]
	s_waitcnt lgkmcnt(2)
	v_mfma_f32_16x16x32_bf16 v[174:177], v[218:221], v[162:165], v[174:177]
	ds_read_b128 v[162:165], v6 offset:8192
	v_mfma_f32_16x16x32_bf16 v[170:173], v[218:221], v[178:181], v[170:173]
	ds_read_b128 v[178:181], v6 offset:10240
	s_waitcnt lgkmcnt(3)
	s_mov_b32 m0, s37
	v_mfma_f32_16x16x32_bf16 v[72:75], v[158:161], v[222:225], v[72:75]
	global_load_lds_dwordx4 v0, s[48:49]
	v_mfma_f32_16x16x32_bf16 v[76:79], v[166:169], v[222:225], v[76:79]
	v_mfma_f32_16x16x32_bf16 v[80:83], v[214:217], v[222:225], v[80:83]
	v_mfma_f32_16x16x32_bf16 v[32:35], v[218:221], v[222:225], v[32:35]
	ds_read_b128 v[222:225], v6 offset:12288
	s_waitcnt lgkmcnt(3)
	v_mfma_f32_16x16x32_bf16 v[88:91], v[158:161], v[226:229], v[88:91]
	s_mov_b32 m0, s39
	v_mfma_f32_16x16x32_bf16 v[92:95], v[166:169], v[226:229], v[92:95]
	global_load_lds_dwordx4 v2, s[46:47]
	v_mfma_f32_16x16x32_bf16 v[96:99], v[214:217], v[226:229], v[96:99]
	v_mfma_f32_16x16x32_bf16 v[36:39], v[218:221], v[226:229], v[36:39]
	ds_read_b128 v[226:229], v6 offset:14336
	s_waitcnt lgkmcnt(3)
	v_mfma_f32_16x16x32_bf16 v[104:107], v[158:161], v[162:165], v[104:107]
	s_waitcnt lgkmcnt(2)
	v_mfma_f32_16x16x32_bf16 v[116:119], v[158:161], v[178:181], v[116:119]
	s_waitcnt lgkmcnt(1)
	s_mov_b32 m0, s40
	v_mfma_f32_16x16x32_bf16 v[128:131], v[158:161], v[222:225], v[128:131]
	global_load_lds_dwordx4 v2, s[48:49]
	s_waitcnt lgkmcnt(0)
	v_mfma_f32_16x16x32_bf16 v[100:103], v[158:161], v[226:229], v[100:103]
	ds_read_b128 v[158:161], v7 offset:33792
	v_mfma_f32_16x16x32_bf16 v[108:111], v[166:169], v[162:165], v[108:111]
	v_mfma_f32_16x16x32_bf16 v[120:123], v[166:169], v[178:181], v[120:123]
	v_mfma_f32_16x16x32_bf16 v[132:135], v[166:169], v[222:225], v[132:135]
	s_mov_b32 m0, s41
	v_mfma_f32_16x16x32_bf16 v[140:143], v[166:169], v[226:229], v[140:143]
	global_load_lds_dwordx4 v4, s[46:47]
	ds_read_b128 v[166:169], v6 offset:1024
	v_mfma_f32_16x16x32_bf16 v[112:115], v[214:217], v[162:165], v[112:115]
	v_mfma_f32_16x16x32_bf16 v[52:55], v[218:221], v[162:165], v[52:55]
	ds_read_b128 v[162:165], v7 offset:35840
	v_mfma_f32_16x16x32_bf16 v[124:127], v[214:217], v[178:181], v[124:127]
	v_mfma_f32_16x16x32_bf16 v[68:71], v[218:221], v[178:181], v[68:71]
	ds_read_b128 v[178:181], v6 offset:3072
	s_mov_b32 m0, s42
	v_mfma_f32_16x16x32_bf16 v[136:139], v[214:217], v[222:225], v[136:139]
	global_load_lds_dwordx4 v4, s[48:49]
	v_mfma_f32_16x16x32_bf16 v[84:87], v[218:221], v[222:225], v[84:87]
	ds_read_b128 v[222:225], v6 offset:5120
	v_mfma_f32_16x16x32_bf16 v[150:153], v[214:217], v[226:229], v[150:153]
	ds_read_b128 v[214:217], v7 offset:37888
	v_mfma_f32_16x16x32_bf16 v[154:157], v[218:221], v[226:229], v[154:157]
	ds_read_b128 v[218:221], v7 offset:39936
	ds_read_b128 v[226:229], v6 offset:7168
	s_waitcnt lgkmcnt(6)
	v_mfma_f32_16x16x32_bf16 v[40:43], v[158:161], v[166:169], v[40:43]
	s_waitcnt lgkmcnt(5)
	s_mov_b32 m0, s43
	v_mfma_f32_16x16x32_bf16 v[44:47], v[162:165], v[166:169], v[44:47]
	global_load_lds_dwordx4 v146, s[46:47]
	s_waitcnt lgkmcnt(4)
	v_mfma_f32_16x16x32_bf16 v[56:59], v[158:161], v[178:181], v[56:59]
	v_mfma_f32_16x16x32_bf16 v[60:63], v[162:165], v[178:181], v[60:63]
	s_waitcnt lgkmcnt(3)
	v_mfma_f32_16x16x32_bf16 v[72:75], v[158:161], v[222:225], v[72:75]
	v_mfma_f32_16x16x32_bf16 v[76:79], v[162:165], v[222:225], v[76:79]
	s_waitcnt lgkmcnt(2)
	s_mov_b32 m0, s44
	v_mfma_f32_16x16x32_bf16 v[48:51], v[214:217], v[166:169], v[48:51]
	global_load_lds_dwordx4 v146, s[48:49]
	s_waitcnt lgkmcnt(1)
	v_mfma_f32_16x16x32_bf16 v[174:177], v[218:221], v[166:169], v[174:177]
	ds_read_b128 v[166:169], v6 offset:9216
	v_mfma_f32_16x16x32_bf16 v[64:67], v[214:217], v[178:181], v[64:67]
	v_mfma_f32_16x16x32_bf16 v[170:173], v[218:221], v[178:181], v[170:173]
	ds_read_b128 v[178:181], v6 offset:11264
	v_mfma_f32_16x16x32_bf16 v[80:83], v[214:217], v[222:225], v[80:83]
	v_mfma_f32_16x16x32_bf16 v[32:35], v[218:221], v[222:225], v[32:35]
	ds_read_b128 v[222:225], v6 offset:13312
	s_waitcnt lgkmcnt(3)
	v_mfma_f32_16x16x32_bf16 v[88:91], v[158:161], v[226:229], v[88:91]
	v_mfma_f32_16x16x32_bf16 v[92:95], v[162:165], v[226:229], v[92:95]
	v_mfma_f32_16x16x32_bf16 v[96:99], v[214:217], v[226:229], v[96:99]
	v_mfma_f32_16x16x32_bf16 v[36:39], v[218:221], v[226:229], v[36:39]
	ds_read_b128 v[226:229], v6 offset:15360
	s_waitcnt lgkmcnt(3)
	v_mfma_f32_16x16x32_bf16 v[104:107], v[158:161], v[166:169], v[104:107]
	v_mfma_f32_16x16x32_bf16 v[108:111], v[162:165], v[166:169], v[108:111]
	v_mfma_f32_16x16x32_bf16 v[112:115], v[214:217], v[166:169], v[112:115]
	v_mfma_f32_16x16x32_bf16 v[52:55], v[218:221], v[166:169], v[52:55]
	s_waitcnt lgkmcnt(2)
	v_mfma_f32_16x16x32_bf16 v[116:119], v[158:161], v[178:181], v[116:119]
	v_mfma_f32_16x16x32_bf16 v[120:123], v[162:165], v[178:181], v[120:123]
	v_mfma_f32_16x16x32_bf16 v[124:127], v[214:217], v[178:181], v[124:127]
	v_mfma_f32_16x16x32_bf16 v[68:71], v[218:221], v[178:181], v[68:71]
	s_waitcnt lgkmcnt(1)
	v_mfma_f32_16x16x32_bf16 v[128:131], v[158:161], v[222:225], v[128:131]
	v_mfma_f32_16x16x32_bf16 v[132:135], v[162:165], v[222:225], v[132:135]
	v_mfma_f32_16x16x32_bf16 v[136:139], v[214:217], v[222:225], v[136:139]
	v_mfma_f32_16x16x32_bf16 v[84:87], v[218:221], v[222:225], v[84:87]
	s_waitcnt lgkmcnt(0)
	v_mfma_f32_16x16x32_bf16 v[100:103], v[158:161], v[226:229], v[100:103]
	v_mfma_f32_16x16x32_bf16 v[140:143], v[162:165], v[226:229], v[140:143]
	v_mfma_f32_16x16x32_bf16 v[150:153], v[214:217], v[226:229], v[150:153]
	v_mfma_f32_16x16x32_bf16 v[154:157], v[218:221], v[226:229], v[154:157]
	s_add_u32 s46, s0, 0x300
	s_addc_u32 s47, s1, 0
	s_add_u32 s48, s14, 0x300
	s_waitcnt vmcnt(0)
	s_barrier
	s_addc_u32 s49, s15, 0
	ds_read_b128 v[158:161], v8
	ds_read_b128 v[162:165], v12
	ds_read_b128 v[166:169], v9
	ds_read_b128 v[178:181], v13
	ds_read_b128 v[214:217], v11
	ds_read_b128 v[218:221], v10
	ds_read_b128 v[222:225], v14
	ds_read_b128 v[226:229], v15
	s_waitcnt lgkmcnt(6)
	v_mfma_f32_16x16x32_bf16 v[40:43], v[158:161], v[162:165], v[40:43]
	s_waitcnt lgkmcnt(5)
	v_mfma_f32_16x16x32_bf16 v[44:47], v[166:169], v[162:165], v[44:47]
	s_waitcnt lgkmcnt(4)
	v_mfma_f32_16x16x32_bf16 v[56:59], v[158:161], v[178:181], v[56:59]
	s_mov_b32 m0, s27
	v_mfma_f32_16x16x32_bf16 v[60:63], v[166:169], v[178:181], v[60:63]
	global_load_lds_dwordx4 v0, s[46:47]
	s_waitcnt lgkmcnt(3)
	v_mfma_f32_16x16x32_bf16 v[48:51], v[214:217], v[162:165], v[48:51]
	v_mfma_f32_16x16x32_bf16 v[64:67], v[214:217], v[178:181], v[64:67]
	s_waitcnt lgkmcnt(2)
	v_mfma_f32_16x16x32_bf16 v[174:177], v[218:221], v[162:165], v[174:177]
	ds_read_b128 v[162:165], v16
	v_mfma_f32_16x16x32_bf16 v[170:173], v[218:221], v[178:181], v[170:173]
	ds_read_b128 v[178:181], v17
	s_waitcnt lgkmcnt(3)
	s_mov_b32 m0, s28
	v_mfma_f32_16x16x32_bf16 v[72:75], v[158:161], v[222:225], v[72:75]
	global_load_lds_dwordx4 v0, s[48:49]
	v_mfma_f32_16x16x32_bf16 v[76:79], v[166:169], v[222:225], v[76:79]
	v_mfma_f32_16x16x32_bf16 v[80:83], v[214:217], v[222:225], v[80:83]
	v_mfma_f32_16x16x32_bf16 v[32:35], v[218:221], v[222:225], v[32:35]
	ds_read_b128 v[222:225], v18
	s_waitcnt lgkmcnt(3)
	v_mfma_f32_16x16x32_bf16 v[88:91], v[158:161], v[226:229], v[88:91]
	s_mov_b32 m0, s29
	v_mfma_f32_16x16x32_bf16 v[92:95], v[166:169], v[226:229], v[92:95]
	global_load_lds_dwordx4 v2, s[46:47]
	v_mfma_f32_16x16x32_bf16 v[96:99], v[214:217], v[226:229], v[96:99]
	v_mfma_f32_16x16x32_bf16 v[36:39], v[218:221], v[226:229], v[36:39]
	ds_read_b128 v[226:229], v19
	s_waitcnt lgkmcnt(3)
	v_mfma_f32_16x16x32_bf16 v[104:107], v[158:161], v[162:165], v[104:107]
	s_waitcnt lgkmcnt(2)
	v_mfma_f32_16x16x32_bf16 v[116:119], v[158:161], v[178:181], v[116:119]
	s_waitcnt lgkmcnt(1)
	s_mov_b32 m0, s30
	v_mfma_f32_16x16x32_bf16 v[128:131], v[158:161], v[222:225], v[128:131]
	global_load_lds_dwordx4 v2, s[48:49]
	s_waitcnt lgkmcnt(0)
	v_mfma_f32_16x16x32_bf16 v[100:103], v[158:161], v[226:229], v[100:103]
	ds_read_b128 v[158:161], v20
	v_mfma_f32_16x16x32_bf16 v[108:111], v[166:169], v[162:165], v[108:111]
	v_mfma_f32_16x16x32_bf16 v[120:123], v[166:169], v[178:181], v[120:123]
	v_mfma_f32_16x16x32_bf16 v[132:135], v[166:169], v[222:225], v[132:135]
	s_mov_b32 m0, s31
	v_mfma_f32_16x16x32_bf16 v[140:143], v[166:169], v[226:229], v[140:143]
	global_load_lds_dwordx4 v4, s[46:47]
	ds_read_b128 v[166:169], v24
	v_mfma_f32_16x16x32_bf16 v[112:115], v[214:217], v[162:165], v[112:115]
	v_mfma_f32_16x16x32_bf16 v[52:55], v[218:221], v[162:165], v[52:55]
	ds_read_b128 v[162:165], v21
	v_mfma_f32_16x16x32_bf16 v[124:127], v[214:217], v[178:181], v[124:127]
	v_mfma_f32_16x16x32_bf16 v[68:71], v[218:221], v[178:181], v[68:71]
	ds_read_b128 v[178:181], v25
	s_mov_b32 m0, s34
	v_mfma_f32_16x16x32_bf16 v[136:139], v[214:217], v[222:225], v[136:139]
	global_load_lds_dwordx4 v4, s[48:49]
	v_mfma_f32_16x16x32_bf16 v[84:87], v[218:221], v[222:225], v[84:87]
	ds_read_b128 v[222:225], v26
	v_mfma_f32_16x16x32_bf16 v[150:153], v[214:217], v[226:229], v[150:153]
	ds_read_b128 v[214:217], v23
	v_mfma_f32_16x16x32_bf16 v[154:157], v[218:221], v[226:229], v[154:157]
	ds_read_b128 v[218:221], v22
	ds_read_b128 v[226:229], v27
	s_waitcnt lgkmcnt(6)
	v_mfma_f32_16x16x32_bf16 v[40:43], v[158:161], v[166:169], v[40:43]
	s_waitcnt lgkmcnt(5)
	s_mov_b32 m0, s35
	v_mfma_f32_16x16x32_bf16 v[44:47], v[162:165], v[166:169], v[44:47]
	global_load_lds_dwordx4 v146, s[46:47]
	s_waitcnt lgkmcnt(4)
	v_mfma_f32_16x16x32_bf16 v[56:59], v[158:161], v[178:181], v[56:59]
	v_mfma_f32_16x16x32_bf16 v[60:63], v[162:165], v[178:181], v[60:63]
	s_waitcnt lgkmcnt(3)
	v_mfma_f32_16x16x32_bf16 v[72:75], v[158:161], v[222:225], v[72:75]
	v_mfma_f32_16x16x32_bf16 v[76:79], v[162:165], v[222:225], v[76:79]
	s_waitcnt lgkmcnt(2)
	s_mov_b32 m0, s36
	v_mfma_f32_16x16x32_bf16 v[48:51], v[214:217], v[166:169], v[48:51]
	global_load_lds_dwordx4 v146, s[48:49]
	s_waitcnt lgkmcnt(1)
	v_mfma_f32_16x16x32_bf16 v[174:177], v[218:221], v[166:169], v[174:177]
	ds_read_b128 v[166:169], v28
	v_mfma_f32_16x16x32_bf16 v[64:67], v[214:217], v[178:181], v[64:67]
	v_mfma_f32_16x16x32_bf16 v[170:173], v[218:221], v[178:181], v[170:173]
	ds_read_b128 v[178:181], v29
	v_mfma_f32_16x16x32_bf16 v[80:83], v[214:217], v[222:225], v[80:83]
	v_mfma_f32_16x16x32_bf16 v[32:35], v[218:221], v[222:225], v[32:35]
	ds_read_b128 v[222:225], v30
	s_waitcnt lgkmcnt(3)
	v_mfma_f32_16x16x32_bf16 v[88:91], v[158:161], v[226:229], v[88:91]
	v_mfma_f32_16x16x32_bf16 v[92:95], v[162:165], v[226:229], v[92:95]
	v_mfma_f32_16x16x32_bf16 v[96:99], v[214:217], v[226:229], v[96:99]
	v_mfma_f32_16x16x32_bf16 v[36:39], v[218:221], v[226:229], v[36:39]
	ds_read_b128 v[226:229], v31
	s_waitcnt lgkmcnt(3)
	v_mfma_f32_16x16x32_bf16 v[104:107], v[158:161], v[166:169], v[104:107]
	v_mfma_f32_16x16x32_bf16 v[108:111], v[162:165], v[166:169], v[108:111]
	v_mfma_f32_16x16x32_bf16 v[112:115], v[214:217], v[166:169], v[112:115]
	v_mfma_f32_16x16x32_bf16 v[52:55], v[218:221], v[166:169], v[52:55]
	s_waitcnt lgkmcnt(2)
	v_mfma_f32_16x16x32_bf16 v[116:119], v[158:161], v[178:181], v[116:119]
	v_mfma_f32_16x16x32_bf16 v[120:123], v[162:165], v[178:181], v[120:123]
	v_mfma_f32_16x16x32_bf16 v[124:127], v[214:217], v[178:181], v[124:127]
	v_mfma_f32_16x16x32_bf16 v[68:71], v[218:221], v[178:181], v[68:71]
	s_waitcnt lgkmcnt(1)
	v_mfma_f32_16x16x32_bf16 v[128:131], v[158:161], v[222:225], v[128:131]
	v_mfma_f32_16x16x32_bf16 v[132:135], v[162:165], v[222:225], v[132:135]
	v_mfma_f32_16x16x32_bf16 v[136:139], v[214:217], v[222:225], v[136:139]
	v_mfma_f32_16x16x32_bf16 v[84:87], v[218:221], v[222:225], v[84:87]
	s_waitcnt lgkmcnt(0)
	v_mfma_f32_16x16x32_bf16 v[100:103], v[158:161], v[226:229], v[100:103]
	v_mfma_f32_16x16x32_bf16 v[140:143], v[162:165], v[226:229], v[140:143]
	v_mfma_f32_16x16x32_bf16 v[150:153], v[214:217], v[226:229], v[150:153]
	v_mfma_f32_16x16x32_bf16 v[154:157], v[218:221], v[226:229], v[154:157]
	s_add_u32 s46, s0, 0x380
	s_addc_u32 s47, s1, 0
	s_add_u32 s48, s14, 0x380
	s_waitcnt vmcnt(0)
	s_barrier
	s_addc_u32 s49, s15, 0
	ds_read_b128 v[158:161], v7 offset:32768
	ds_read_b128 v[162:165], v6
	ds_read_b128 v[166:169], v7 offset:34816
	ds_read_b128 v[178:181], v6 offset:2048
	ds_read_b128 v[214:217], v7 offset:36864
	ds_read_b128 v[218:221], v7 offset:38912
	ds_read_b128 v[222:225], v6 offset:4096
	ds_read_b128 v[226:229], v6 offset:6144
	s_waitcnt lgkmcnt(6)
	v_mfma_f32_16x16x32_bf16 v[40:43], v[158:161], v[162:165], v[40:43]
	s_waitcnt lgkmcnt(5)
	v_mfma_f32_16x16x32_bf16 v[44:47], v[166:169], v[162:165], v[44:47]
	s_waitcnt lgkmcnt(4)
	v_mfma_f32_16x16x32_bf16 v[56:59], v[158:161], v[178:181], v[56:59]
	s_mov_b32 m0, s38
	v_mfma_f32_16x16x32_bf16 v[60:63], v[166:169], v[178:181], v[60:63]
	global_load_lds_dwordx4 v0, s[46:47]
	s_waitcnt lgkmcnt(3)
	v_mfma_f32_16x16x32_bf16 v[48:51], v[214:217], v[162:165], v[48:51]
	v_mfma_f32_16x16x32_bf16 v[64:67], v[214:217], v[178:181], v[64:67]
	s_waitcnt lgkmcnt(2)
	v_mfma_f32_16x16x32_bf16 v[174:177], v[218:221], v[162:165], v[174:177]
	ds_read_b128 v[162:165], v6 offset:8192
	v_mfma_f32_16x16x32_bf16 v[170:173], v[218:221], v[178:181], v[170:173]
	ds_read_b128 v[178:181], v6 offset:10240
	s_waitcnt lgkmcnt(3)
	s_mov_b32 m0, s37
	v_mfma_f32_16x16x32_bf16 v[72:75], v[158:161], v[222:225], v[72:75]
	global_load_lds_dwordx4 v0, s[48:49]
	v_mfma_f32_16x16x32_bf16 v[76:79], v[166:169], v[222:225], v[76:79]
	v_mfma_f32_16x16x32_bf16 v[80:83], v[214:217], v[222:225], v[80:83]
	v_mfma_f32_16x16x32_bf16 v[32:35], v[218:221], v[222:225], v[32:35]
	ds_read_b128 v[222:225], v6 offset:12288
	s_waitcnt lgkmcnt(3)
	v_mfma_f32_16x16x32_bf16 v[88:91], v[158:161], v[226:229], v[88:91]
	s_mov_b32 m0, s39
	v_mfma_f32_16x16x32_bf16 v[92:95], v[166:169], v[226:229], v[92:95]
	global_load_lds_dwordx4 v2, s[46:47]
	v_mfma_f32_16x16x32_bf16 v[96:99], v[214:217], v[226:229], v[96:99]
	v_mfma_f32_16x16x32_bf16 v[36:39], v[218:221], v[226:229], v[36:39]
	ds_read_b128 v[226:229], v6 offset:14336
	s_waitcnt lgkmcnt(3)
	v_mfma_f32_16x16x32_bf16 v[104:107], v[158:161], v[162:165], v[104:107]
	s_waitcnt lgkmcnt(2)
	v_mfma_f32_16x16x32_bf16 v[116:119], v[158:161], v[178:181], v[116:119]
	s_waitcnt lgkmcnt(1)
	s_mov_b32 m0, s40
	v_mfma_f32_16x16x32_bf16 v[128:131], v[158:161], v[222:225], v[128:131]
	global_load_lds_dwordx4 v2, s[48:49]
	s_waitcnt lgkmcnt(0)
	v_mfma_f32_16x16x32_bf16 v[100:103], v[158:161], v[226:229], v[100:103]
	ds_read_b128 v[158:161], v7 offset:33792
	v_mfma_f32_16x16x32_bf16 v[108:111], v[166:169], v[162:165], v[108:111]
	v_mfma_f32_16x16x32_bf16 v[120:123], v[166:169], v[178:181], v[120:123]
	v_mfma_f32_16x16x32_bf16 v[132:135], v[166:169], v[222:225], v[132:135]
	s_mov_b32 m0, s41
	v_mfma_f32_16x16x32_bf16 v[140:143], v[166:169], v[226:229], v[140:143]
	global_load_lds_dwordx4 v4, s[46:47]
	ds_read_b128 v[166:169], v6 offset:1024
	v_mfma_f32_16x16x32_bf16 v[112:115], v[214:217], v[162:165], v[112:115]
	v_mfma_f32_16x16x32_bf16 v[52:55], v[218:221], v[162:165], v[52:55]
	ds_read_b128 v[162:165], v7 offset:35840
	v_mfma_f32_16x16x32_bf16 v[124:127], v[214:217], v[178:181], v[124:127]
	v_mfma_f32_16x16x32_bf16 v[68:71], v[218:221], v[178:181], v[68:71]
	ds_read_b128 v[178:181], v6 offset:3072
	s_mov_b32 m0, s42
	v_mfma_f32_16x16x32_bf16 v[136:139], v[214:217], v[222:225], v[136:139]
	global_load_lds_dwordx4 v4, s[48:49]
	v_mfma_f32_16x16x32_bf16 v[84:87], v[218:221], v[222:225], v[84:87]
	ds_read_b128 v[222:225], v6 offset:5120
	v_mfma_f32_16x16x32_bf16 v[150:153], v[214:217], v[226:229], v[150:153]
	ds_read_b128 v[214:217], v7 offset:37888
	v_mfma_f32_16x16x32_bf16 v[154:157], v[218:221], v[226:229], v[154:157]
	ds_read_b128 v[218:221], v7 offset:39936
	ds_read_b128 v[226:229], v6 offset:7168
	s_waitcnt lgkmcnt(6)
	v_mfma_f32_16x16x32_bf16 v[40:43], v[158:161], v[166:169], v[40:43]
	s_waitcnt lgkmcnt(5)
	s_mov_b32 m0, s43
	v_mfma_f32_16x16x32_bf16 v[44:47], v[162:165], v[166:169], v[44:47]
	global_load_lds_dwordx4 v146, s[46:47]
	s_waitcnt lgkmcnt(4)
	v_mfma_f32_16x16x32_bf16 v[56:59], v[158:161], v[178:181], v[56:59]
	v_mfma_f32_16x16x32_bf16 v[60:63], v[162:165], v[178:181], v[60:63]
	s_waitcnt lgkmcnt(3)
	v_mfma_f32_16x16x32_bf16 v[72:75], v[158:161], v[222:225], v[72:75]
	v_mfma_f32_16x16x32_bf16 v[76:79], v[162:165], v[222:225], v[76:79]
	s_waitcnt lgkmcnt(2)
	s_mov_b32 m0, s44
	v_mfma_f32_16x16x32_bf16 v[48:51], v[214:217], v[166:169], v[48:51]
	global_load_lds_dwordx4 v146, s[48:49]
	s_waitcnt lgkmcnt(1)
	v_mfma_f32_16x16x32_bf16 v[174:177], v[218:221], v[166:169], v[174:177]
	ds_read_b128 v[166:169], v6 offset:9216
	v_mfma_f32_16x16x32_bf16 v[64:67], v[214:217], v[178:181], v[64:67]
	v_mfma_f32_16x16x32_bf16 v[170:173], v[218:221], v[178:181], v[170:173]
	ds_read_b128 v[178:181], v6 offset:11264
	v_mfma_f32_16x16x32_bf16 v[80:83], v[214:217], v[222:225], v[80:83]
	v_mfma_f32_16x16x32_bf16 v[32:35], v[218:221], v[222:225], v[32:35]
	ds_read_b128 v[222:225], v6 offset:13312
	s_waitcnt lgkmcnt(3)
	v_mfma_f32_16x16x32_bf16 v[88:91], v[158:161], v[226:229], v[88:91]
	v_mfma_f32_16x16x32_bf16 v[92:95], v[162:165], v[226:229], v[92:95]
	v_mfma_f32_16x16x32_bf16 v[96:99], v[214:217], v[226:229], v[96:99]
	v_mfma_f32_16x16x32_bf16 v[36:39], v[218:221], v[226:229], v[36:39]
	ds_read_b128 v[226:229], v6 offset:15360
	s_waitcnt lgkmcnt(3)
	v_mfma_f32_16x16x32_bf16 v[104:107], v[158:161], v[166:169], v[104:107]
	v_mfma_f32_16x16x32_bf16 v[108:111], v[162:165], v[166:169], v[108:111]
	v_mfma_f32_16x16x32_bf16 v[112:115], v[214:217], v[166:169], v[112:115]
	v_mfma_f32_16x16x32_bf16 v[52:55], v[218:221], v[166:169], v[52:55]
	s_waitcnt lgkmcnt(2)
	v_mfma_f32_16x16x32_bf16 v[116:119], v[158:161], v[178:181], v[116:119]
	v_mfma_f32_16x16x32_bf16 v[120:123], v[162:165], v[178:181], v[120:123]
	v_mfma_f32_16x16x32_bf16 v[124:127], v[214:217], v[178:181], v[124:127]
	v_mfma_f32_16x16x32_bf16 v[68:71], v[218:221], v[178:181], v[68:71]
	s_waitcnt lgkmcnt(1)
	v_mfma_f32_16x16x32_bf16 v[128:131], v[158:161], v[222:225], v[128:131]
	v_mfma_f32_16x16x32_bf16 v[132:135], v[162:165], v[222:225], v[132:135]
	v_mfma_f32_16x16x32_bf16 v[136:139], v[214:217], v[222:225], v[136:139]
	v_mfma_f32_16x16x32_bf16 v[84:87], v[218:221], v[222:225], v[84:87]
	s_waitcnt lgkmcnt(0)
	v_mfma_f32_16x16x32_bf16 v[100:103], v[158:161], v[226:229], v[100:103]
	v_mfma_f32_16x16x32_bf16 v[140:143], v[162:165], v[226:229], v[140:143]
	v_mfma_f32_16x16x32_bf16 v[150:153], v[214:217], v[226:229], v[150:153]
	v_mfma_f32_16x16x32_bf16 v[154:157], v[218:221], v[226:229], v[154:157]
	s_add_u32 s46, s0, 0x400
	s_addc_u32 s47, s1, 0
	s_add_u32 s48, s14, 0x400
	s_waitcnt vmcnt(0)
	s_barrier
	s_addc_u32 s49, s15, 0
	ds_read_b128 v[158:161], v8
	ds_read_b128 v[162:165], v12
	ds_read_b128 v[166:169], v9
	ds_read_b128 v[178:181], v13
	ds_read_b128 v[214:217], v11
	ds_read_b128 v[218:221], v10
	ds_read_b128 v[222:225], v14
	ds_read_b128 v[226:229], v15
	s_waitcnt lgkmcnt(6)
	v_mfma_f32_16x16x32_bf16 v[40:43], v[158:161], v[162:165], v[40:43]
	s_waitcnt lgkmcnt(5)
	v_mfma_f32_16x16x32_bf16 v[44:47], v[166:169], v[162:165], v[44:47]
	s_waitcnt lgkmcnt(4)
	v_mfma_f32_16x16x32_bf16 v[56:59], v[158:161], v[178:181], v[56:59]
	s_mov_b32 m0, s27
	v_mfma_f32_16x16x32_bf16 v[60:63], v[166:169], v[178:181], v[60:63]
	global_load_lds_dwordx4 v0, s[46:47]
	s_waitcnt lgkmcnt(3)
	v_mfma_f32_16x16x32_bf16 v[48:51], v[214:217], v[162:165], v[48:51]
	v_mfma_f32_16x16x32_bf16 v[64:67], v[214:217], v[178:181], v[64:67]
	s_waitcnt lgkmcnt(2)
	v_mfma_f32_16x16x32_bf16 v[174:177], v[218:221], v[162:165], v[174:177]
	ds_read_b128 v[162:165], v16
	v_mfma_f32_16x16x32_bf16 v[170:173], v[218:221], v[178:181], v[170:173]
	ds_read_b128 v[178:181], v17
	s_waitcnt lgkmcnt(3)
	s_mov_b32 m0, s28
	v_mfma_f32_16x16x32_bf16 v[72:75], v[158:161], v[222:225], v[72:75]
	global_load_lds_dwordx4 v0, s[48:49]
	v_mfma_f32_16x16x32_bf16 v[76:79], v[166:169], v[222:225], v[76:79]
	v_mfma_f32_16x16x32_bf16 v[80:83], v[214:217], v[222:225], v[80:83]
	v_mfma_f32_16x16x32_bf16 v[32:35], v[218:221], v[222:225], v[32:35]
	ds_read_b128 v[222:225], v18
	s_waitcnt lgkmcnt(3)
	v_mfma_f32_16x16x32_bf16 v[88:91], v[158:161], v[226:229], v[88:91]
	s_mov_b32 m0, s29
	v_mfma_f32_16x16x32_bf16 v[92:95], v[166:169], v[226:229], v[92:95]
	global_load_lds_dwordx4 v2, s[46:47]
	v_mfma_f32_16x16x32_bf16 v[96:99], v[214:217], v[226:229], v[96:99]
	v_mfma_f32_16x16x32_bf16 v[36:39], v[218:221], v[226:229], v[36:39]
	ds_read_b128 v[226:229], v19
	s_waitcnt lgkmcnt(3)
	v_mfma_f32_16x16x32_bf16 v[104:107], v[158:161], v[162:165], v[104:107]
	s_waitcnt lgkmcnt(2)
	v_mfma_f32_16x16x32_bf16 v[116:119], v[158:161], v[178:181], v[116:119]
	s_waitcnt lgkmcnt(1)
	s_mov_b32 m0, s30
	v_mfma_f32_16x16x32_bf16 v[128:131], v[158:161], v[222:225], v[128:131]
	global_load_lds_dwordx4 v2, s[48:49]
	s_waitcnt lgkmcnt(0)
	v_mfma_f32_16x16x32_bf16 v[100:103], v[158:161], v[226:229], v[100:103]
	ds_read_b128 v[158:161], v20
	v_mfma_f32_16x16x32_bf16 v[108:111], v[166:169], v[162:165], v[108:111]
	v_mfma_f32_16x16x32_bf16 v[120:123], v[166:169], v[178:181], v[120:123]
	v_mfma_f32_16x16x32_bf16 v[132:135], v[166:169], v[222:225], v[132:135]
	s_mov_b32 m0, s31
	v_mfma_f32_16x16x32_bf16 v[140:143], v[166:169], v[226:229], v[140:143]
	global_load_lds_dwordx4 v4, s[46:47]
	ds_read_b128 v[166:169], v24
	v_mfma_f32_16x16x32_bf16 v[112:115], v[214:217], v[162:165], v[112:115]
	v_mfma_f32_16x16x32_bf16 v[52:55], v[218:221], v[162:165], v[52:55]
	ds_read_b128 v[162:165], v21
	v_mfma_f32_16x16x32_bf16 v[124:127], v[214:217], v[178:181], v[124:127]
	v_mfma_f32_16x16x32_bf16 v[68:71], v[218:221], v[178:181], v[68:71]
	ds_read_b128 v[178:181], v25
	s_mov_b32 m0, s34
	v_mfma_f32_16x16x32_bf16 v[136:139], v[214:217], v[222:225], v[136:139]
	global_load_lds_dwordx4 v4, s[48:49]
	v_mfma_f32_16x16x32_bf16 v[84:87], v[218:221], v[222:225], v[84:87]
	ds_read_b128 v[222:225], v26
	v_mfma_f32_16x16x32_bf16 v[150:153], v[214:217], v[226:229], v[150:153]
	ds_read_b128 v[214:217], v23
	v_mfma_f32_16x16x32_bf16 v[154:157], v[218:221], v[226:229], v[154:157]
	ds_read_b128 v[218:221], v22
	ds_read_b128 v[226:229], v27
	s_waitcnt lgkmcnt(6)
	v_mfma_f32_16x16x32_bf16 v[40:43], v[158:161], v[166:169], v[40:43]
	s_waitcnt lgkmcnt(5)
	s_mov_b32 m0, s35
	v_mfma_f32_16x16x32_bf16 v[44:47], v[162:165], v[166:169], v[44:47]
	global_load_lds_dwordx4 v146, s[46:47]
	s_waitcnt lgkmcnt(4)
	v_mfma_f32_16x16x32_bf16 v[56:59], v[158:161], v[178:181], v[56:59]
	v_mfma_f32_16x16x32_bf16 v[60:63], v[162:165], v[178:181], v[60:63]
	s_waitcnt lgkmcnt(3)
	v_mfma_f32_16x16x32_bf16 v[72:75], v[158:161], v[222:225], v[72:75]
	v_mfma_f32_16x16x32_bf16 v[76:79], v[162:165], v[222:225], v[76:79]
	s_waitcnt lgkmcnt(2)
	s_mov_b32 m0, s36
	v_mfma_f32_16x16x32_bf16 v[48:51], v[214:217], v[166:169], v[48:51]
	global_load_lds_dwordx4 v146, s[48:49]
	s_waitcnt lgkmcnt(1)
	v_mfma_f32_16x16x32_bf16 v[174:177], v[218:221], v[166:169], v[174:177]
	ds_read_b128 v[166:169], v28
	v_mfma_f32_16x16x32_bf16 v[64:67], v[214:217], v[178:181], v[64:67]
	v_mfma_f32_16x16x32_bf16 v[170:173], v[218:221], v[178:181], v[170:173]
	ds_read_b128 v[178:181], v29
	v_mfma_f32_16x16x32_bf16 v[80:83], v[214:217], v[222:225], v[80:83]
	v_mfma_f32_16x16x32_bf16 v[32:35], v[218:221], v[222:225], v[32:35]
	ds_read_b128 v[222:225], v30
	s_waitcnt lgkmcnt(3)
	v_mfma_f32_16x16x32_bf16 v[88:91], v[158:161], v[226:229], v[88:91]
	v_mfma_f32_16x16x32_bf16 v[92:95], v[162:165], v[226:229], v[92:95]
	v_mfma_f32_16x16x32_bf16 v[96:99], v[214:217], v[226:229], v[96:99]
	v_mfma_f32_16x16x32_bf16 v[36:39], v[218:221], v[226:229], v[36:39]
	ds_read_b128 v[226:229], v31
	s_waitcnt lgkmcnt(3)
	v_mfma_f32_16x16x32_bf16 v[104:107], v[158:161], v[166:169], v[104:107]
	v_mfma_f32_16x16x32_bf16 v[108:111], v[162:165], v[166:169], v[108:111]
	v_mfma_f32_16x16x32_bf16 v[112:115], v[214:217], v[166:169], v[112:115]
	v_mfma_f32_16x16x32_bf16 v[52:55], v[218:221], v[166:169], v[52:55]
	s_waitcnt lgkmcnt(2)
	v_mfma_f32_16x16x32_bf16 v[116:119], v[158:161], v[178:181], v[116:119]
	v_mfma_f32_16x16x32_bf16 v[120:123], v[162:165], v[178:181], v[120:123]
	v_mfma_f32_16x16x32_bf16 v[124:127], v[214:217], v[178:181], v[124:127]
	v_mfma_f32_16x16x32_bf16 v[68:71], v[218:221], v[178:181], v[68:71]
	s_waitcnt lgkmcnt(1)
	v_mfma_f32_16x16x32_bf16 v[128:131], v[158:161], v[222:225], v[128:131]
	v_mfma_f32_16x16x32_bf16 v[132:135], v[162:165], v[222:225], v[132:135]
	v_mfma_f32_16x16x32_bf16 v[136:139], v[214:217], v[222:225], v[136:139]
	v_mfma_f32_16x16x32_bf16 v[84:87], v[218:221], v[222:225], v[84:87]
	s_waitcnt lgkmcnt(0)
	v_mfma_f32_16x16x32_bf16 v[100:103], v[158:161], v[226:229], v[100:103]
	v_mfma_f32_16x16x32_bf16 v[140:143], v[162:165], v[226:229], v[140:143]
	v_mfma_f32_16x16x32_bf16 v[150:153], v[214:217], v[226:229], v[150:153]
	v_mfma_f32_16x16x32_bf16 v[154:157], v[218:221], v[226:229], v[154:157]
	s_add_u32 s46, s0, 0x480
	s_addc_u32 s47, s1, 0
	s_add_u32 s48, s14, 0x480
	s_waitcnt vmcnt(0)
	s_barrier
	s_addc_u32 s49, s15, 0
	ds_read_b128 v[158:161], v7 offset:32768
	ds_read_b128 v[162:165], v6
	ds_read_b128 v[166:169], v7 offset:34816
	ds_read_b128 v[178:181], v6 offset:2048
	ds_read_b128 v[214:217], v7 offset:36864
	ds_read_b128 v[218:221], v7 offset:38912
	ds_read_b128 v[222:225], v6 offset:4096
	ds_read_b128 v[226:229], v6 offset:6144
	s_waitcnt lgkmcnt(6)
	v_mfma_f32_16x16x32_bf16 v[40:43], v[158:161], v[162:165], v[40:43]
	s_waitcnt lgkmcnt(5)
	v_mfma_f32_16x16x32_bf16 v[44:47], v[166:169], v[162:165], v[44:47]
	s_waitcnt lgkmcnt(4)
	v_mfma_f32_16x16x32_bf16 v[56:59], v[158:161], v[178:181], v[56:59]
	s_mov_b32 m0, s38
	v_mfma_f32_16x16x32_bf16 v[60:63], v[166:169], v[178:181], v[60:63]
	global_load_lds_dwordx4 v0, s[46:47]
	s_waitcnt lgkmcnt(3)
	v_mfma_f32_16x16x32_bf16 v[48:51], v[214:217], v[162:165], v[48:51]
	v_mfma_f32_16x16x32_bf16 v[64:67], v[214:217], v[178:181], v[64:67]
	s_waitcnt lgkmcnt(2)
	v_mfma_f32_16x16x32_bf16 v[174:177], v[218:221], v[162:165], v[174:177]
	ds_read_b128 v[162:165], v6 offset:8192
	v_mfma_f32_16x16x32_bf16 v[170:173], v[218:221], v[178:181], v[170:173]
	ds_read_b128 v[178:181], v6 offset:10240
	s_waitcnt lgkmcnt(3)
	s_mov_b32 m0, s37
	v_mfma_f32_16x16x32_bf16 v[72:75], v[158:161], v[222:225], v[72:75]
	global_load_lds_dwordx4 v0, s[48:49]
	v_mfma_f32_16x16x32_bf16 v[76:79], v[166:169], v[222:225], v[76:79]
	v_mfma_f32_16x16x32_bf16 v[80:83], v[214:217], v[222:225], v[80:83]
	v_mfma_f32_16x16x32_bf16 v[32:35], v[218:221], v[222:225], v[32:35]
	ds_read_b128 v[222:225], v6 offset:12288
	s_waitcnt lgkmcnt(3)
	v_mfma_f32_16x16x32_bf16 v[88:91], v[158:161], v[226:229], v[88:91]
	s_mov_b32 m0, s39
	v_mfma_f32_16x16x32_bf16 v[92:95], v[166:169], v[226:229], v[92:95]
	global_load_lds_dwordx4 v2, s[46:47]
	v_mfma_f32_16x16x32_bf16 v[96:99], v[214:217], v[226:229], v[96:99]
	v_mfma_f32_16x16x32_bf16 v[36:39], v[218:221], v[226:229], v[36:39]
	ds_read_b128 v[226:229], v6 offset:14336
	s_waitcnt lgkmcnt(3)
	v_mfma_f32_16x16x32_bf16 v[104:107], v[158:161], v[162:165], v[104:107]
	s_waitcnt lgkmcnt(2)
	v_mfma_f32_16x16x32_bf16 v[116:119], v[158:161], v[178:181], v[116:119]
	s_waitcnt lgkmcnt(1)
	s_mov_b32 m0, s40
	v_mfma_f32_16x16x32_bf16 v[128:131], v[158:161], v[222:225], v[128:131]
	global_load_lds_dwordx4 v2, s[48:49]
	s_waitcnt lgkmcnt(0)
	v_mfma_f32_16x16x32_bf16 v[100:103], v[158:161], v[226:229], v[100:103]
	ds_read_b128 v[158:161], v7 offset:33792
	v_mfma_f32_16x16x32_bf16 v[108:111], v[166:169], v[162:165], v[108:111]
	v_mfma_f32_16x16x32_bf16 v[120:123], v[166:169], v[178:181], v[120:123]
	v_mfma_f32_16x16x32_bf16 v[132:135], v[166:169], v[222:225], v[132:135]
	s_mov_b32 m0, s41
	v_mfma_f32_16x16x32_bf16 v[140:143], v[166:169], v[226:229], v[140:143]
	global_load_lds_dwordx4 v4, s[46:47]
	ds_read_b128 v[166:169], v6 offset:1024
	v_mfma_f32_16x16x32_bf16 v[112:115], v[214:217], v[162:165], v[112:115]
	v_mfma_f32_16x16x32_bf16 v[52:55], v[218:221], v[162:165], v[52:55]
	ds_read_b128 v[162:165], v7 offset:35840
	v_mfma_f32_16x16x32_bf16 v[124:127], v[214:217], v[178:181], v[124:127]
	v_mfma_f32_16x16x32_bf16 v[68:71], v[218:221], v[178:181], v[68:71]
	ds_read_b128 v[178:181], v6 offset:3072
	s_mov_b32 m0, s42
	v_mfma_f32_16x16x32_bf16 v[136:139], v[214:217], v[222:225], v[136:139]
	global_load_lds_dwordx4 v4, s[48:49]
	v_mfma_f32_16x16x32_bf16 v[84:87], v[218:221], v[222:225], v[84:87]
	ds_read_b128 v[222:225], v6 offset:5120
	v_mfma_f32_16x16x32_bf16 v[150:153], v[214:217], v[226:229], v[150:153]
	ds_read_b128 v[214:217], v7 offset:37888
	v_mfma_f32_16x16x32_bf16 v[154:157], v[218:221], v[226:229], v[154:157]
	ds_read_b128 v[218:221], v7 offset:39936
	ds_read_b128 v[226:229], v6 offset:7168
	s_waitcnt lgkmcnt(6)
	v_mfma_f32_16x16x32_bf16 v[40:43], v[158:161], v[166:169], v[40:43]
	s_waitcnt lgkmcnt(5)
	s_mov_b32 m0, s43
	v_mfma_f32_16x16x32_bf16 v[44:47], v[162:165], v[166:169], v[44:47]
	global_load_lds_dwordx4 v146, s[46:47]
	s_waitcnt lgkmcnt(4)
	v_mfma_f32_16x16x32_bf16 v[56:59], v[158:161], v[178:181], v[56:59]
	v_mfma_f32_16x16x32_bf16 v[60:63], v[162:165], v[178:181], v[60:63]
	s_waitcnt lgkmcnt(3)
	v_mfma_f32_16x16x32_bf16 v[72:75], v[158:161], v[222:225], v[72:75]
	v_mfma_f32_16x16x32_bf16 v[76:79], v[162:165], v[222:225], v[76:79]
	s_waitcnt lgkmcnt(2)
	s_mov_b32 m0, s44
	v_mfma_f32_16x16x32_bf16 v[48:51], v[214:217], v[166:169], v[48:51]
	global_load_lds_dwordx4 v146, s[48:49]
	s_waitcnt lgkmcnt(1)
	v_mfma_f32_16x16x32_bf16 v[174:177], v[218:221], v[166:169], v[174:177]
	ds_read_b128 v[166:169], v6 offset:9216
	v_mfma_f32_16x16x32_bf16 v[64:67], v[214:217], v[178:181], v[64:67]
	v_mfma_f32_16x16x32_bf16 v[170:173], v[218:221], v[178:181], v[170:173]
	ds_read_b128 v[178:181], v6 offset:11264
	v_mfma_f32_16x16x32_bf16 v[80:83], v[214:217], v[222:225], v[80:83]
	v_mfma_f32_16x16x32_bf16 v[32:35], v[218:221], v[222:225], v[32:35]
	ds_read_b128 v[222:225], v6 offset:13312
	s_waitcnt lgkmcnt(3)
	v_mfma_f32_16x16x32_bf16 v[88:91], v[158:161], v[226:229], v[88:91]
	v_mfma_f32_16x16x32_bf16 v[92:95], v[162:165], v[226:229], v[92:95]
	v_mfma_f32_16x16x32_bf16 v[96:99], v[214:217], v[226:229], v[96:99]
	v_mfma_f32_16x16x32_bf16 v[36:39], v[218:221], v[226:229], v[36:39]
	ds_read_b128 v[226:229], v6 offset:15360
	s_waitcnt lgkmcnt(3)
	v_mfma_f32_16x16x32_bf16 v[104:107], v[158:161], v[166:169], v[104:107]
	v_mfma_f32_16x16x32_bf16 v[108:111], v[162:165], v[166:169], v[108:111]
	v_mfma_f32_16x16x32_bf16 v[112:115], v[214:217], v[166:169], v[112:115]
	v_mfma_f32_16x16x32_bf16 v[52:55], v[218:221], v[166:169], v[52:55]
	s_waitcnt lgkmcnt(2)
	v_mfma_f32_16x16x32_bf16 v[116:119], v[158:161], v[178:181], v[116:119]
	v_mfma_f32_16x16x32_bf16 v[120:123], v[162:165], v[178:181], v[120:123]
	v_mfma_f32_16x16x32_bf16 v[124:127], v[214:217], v[178:181], v[124:127]
	v_mfma_f32_16x16x32_bf16 v[68:71], v[218:221], v[178:181], v[68:71]
	s_waitcnt lgkmcnt(1)
	v_mfma_f32_16x16x32_bf16 v[128:131], v[158:161], v[222:225], v[128:131]
	v_mfma_f32_16x16x32_bf16 v[132:135], v[162:165], v[222:225], v[132:135]
	v_mfma_f32_16x16x32_bf16 v[136:139], v[214:217], v[222:225], v[136:139]
	v_mfma_f32_16x16x32_bf16 v[84:87], v[218:221], v[222:225], v[84:87]
	s_waitcnt lgkmcnt(0)
	v_mfma_f32_16x16x32_bf16 v[100:103], v[158:161], v[226:229], v[100:103]
	v_mfma_f32_16x16x32_bf16 v[140:143], v[162:165], v[226:229], v[140:143]
	v_mfma_f32_16x16x32_bf16 v[150:153], v[214:217], v[226:229], v[150:153]
	v_mfma_f32_16x16x32_bf16 v[154:157], v[218:221], v[226:229], v[154:157]
	s_add_u32 s46, s0, 0x500
	s_addc_u32 s47, s1, 0
	s_add_u32 s48, s14, 0x500
	s_waitcnt vmcnt(0)
	s_barrier
	s_addc_u32 s49, s15, 0
	ds_read_b128 v[158:161], v8
	ds_read_b128 v[162:165], v12
	ds_read_b128 v[166:169], v9
	ds_read_b128 v[178:181], v13
	ds_read_b128 v[214:217], v11
	ds_read_b128 v[218:221], v10
	ds_read_b128 v[222:225], v14
	ds_read_b128 v[226:229], v15
	s_waitcnt lgkmcnt(6)
	v_mfma_f32_16x16x32_bf16 v[40:43], v[158:161], v[162:165], v[40:43]
	s_waitcnt lgkmcnt(5)
	v_mfma_f32_16x16x32_bf16 v[44:47], v[166:169], v[162:165], v[44:47]
	s_waitcnt lgkmcnt(4)
	v_mfma_f32_16x16x32_bf16 v[56:59], v[158:161], v[178:181], v[56:59]
	s_mov_b32 m0, s27
	v_mfma_f32_16x16x32_bf16 v[60:63], v[166:169], v[178:181], v[60:63]
	global_load_lds_dwordx4 v0, s[46:47]
	s_waitcnt lgkmcnt(3)
	v_mfma_f32_16x16x32_bf16 v[48:51], v[214:217], v[162:165], v[48:51]
	v_mfma_f32_16x16x32_bf16 v[64:67], v[214:217], v[178:181], v[64:67]
	s_waitcnt lgkmcnt(2)
	v_mfma_f32_16x16x32_bf16 v[174:177], v[218:221], v[162:165], v[174:177]
	ds_read_b128 v[162:165], v16
	v_mfma_f32_16x16x32_bf16 v[170:173], v[218:221], v[178:181], v[170:173]
	ds_read_b128 v[178:181], v17
	s_waitcnt lgkmcnt(3)
	s_mov_b32 m0, s28
	v_mfma_f32_16x16x32_bf16 v[72:75], v[158:161], v[222:225], v[72:75]
	global_load_lds_dwordx4 v0, s[48:49]
	v_mfma_f32_16x16x32_bf16 v[76:79], v[166:169], v[222:225], v[76:79]
	v_mfma_f32_16x16x32_bf16 v[80:83], v[214:217], v[222:225], v[80:83]
	v_mfma_f32_16x16x32_bf16 v[32:35], v[218:221], v[222:225], v[32:35]
	ds_read_b128 v[222:225], v18
	s_waitcnt lgkmcnt(3)
	v_mfma_f32_16x16x32_bf16 v[88:91], v[158:161], v[226:229], v[88:91]
	s_mov_b32 m0, s29
	v_mfma_f32_16x16x32_bf16 v[92:95], v[166:169], v[226:229], v[92:95]
	global_load_lds_dwordx4 v2, s[46:47]
	v_mfma_f32_16x16x32_bf16 v[96:99], v[214:217], v[226:229], v[96:99]
	v_mfma_f32_16x16x32_bf16 v[36:39], v[218:221], v[226:229], v[36:39]
	ds_read_b128 v[226:229], v19
	s_waitcnt lgkmcnt(3)
	v_mfma_f32_16x16x32_bf16 v[104:107], v[158:161], v[162:165], v[104:107]
	s_waitcnt lgkmcnt(2)
	v_mfma_f32_16x16x32_bf16 v[116:119], v[158:161], v[178:181], v[116:119]
	s_waitcnt lgkmcnt(1)
	s_mov_b32 m0, s30
	v_mfma_f32_16x16x32_bf16 v[128:131], v[158:161], v[222:225], v[128:131]
	global_load_lds_dwordx4 v2, s[48:49]
	s_waitcnt lgkmcnt(0)
	v_mfma_f32_16x16x32_bf16 v[100:103], v[158:161], v[226:229], v[100:103]
	ds_read_b128 v[158:161], v20
	v_mfma_f32_16x16x32_bf16 v[108:111], v[166:169], v[162:165], v[108:111]
	v_mfma_f32_16x16x32_bf16 v[120:123], v[166:169], v[178:181], v[120:123]
	v_mfma_f32_16x16x32_bf16 v[132:135], v[166:169], v[222:225], v[132:135]
	s_mov_b32 m0, s31
	v_mfma_f32_16x16x32_bf16 v[140:143], v[166:169], v[226:229], v[140:143]
	global_load_lds_dwordx4 v4, s[46:47]
	ds_read_b128 v[166:169], v24
	v_mfma_f32_16x16x32_bf16 v[112:115], v[214:217], v[162:165], v[112:115]
	v_mfma_f32_16x16x32_bf16 v[52:55], v[218:221], v[162:165], v[52:55]
	ds_read_b128 v[162:165], v21
	v_mfma_f32_16x16x32_bf16 v[124:127], v[214:217], v[178:181], v[124:127]
	v_mfma_f32_16x16x32_bf16 v[68:71], v[218:221], v[178:181], v[68:71]
	ds_read_b128 v[178:181], v25
	s_mov_b32 m0, s34
	v_mfma_f32_16x16x32_bf16 v[136:139], v[214:217], v[222:225], v[136:139]
	global_load_lds_dwordx4 v4, s[48:49]
	v_mfma_f32_16x16x32_bf16 v[84:87], v[218:221], v[222:225], v[84:87]
	ds_read_b128 v[222:225], v26
	v_mfma_f32_16x16x32_bf16 v[150:153], v[214:217], v[226:229], v[150:153]
	ds_read_b128 v[214:217], v23
	v_mfma_f32_16x16x32_bf16 v[154:157], v[218:221], v[226:229], v[154:157]
	ds_read_b128 v[218:221], v22
	ds_read_b128 v[226:229], v27
	s_waitcnt lgkmcnt(6)
	v_mfma_f32_16x16x32_bf16 v[40:43], v[158:161], v[166:169], v[40:43]
	s_waitcnt lgkmcnt(5)
	s_mov_b32 m0, s35
	v_mfma_f32_16x16x32_bf16 v[44:47], v[162:165], v[166:169], v[44:47]
	global_load_lds_dwordx4 v146, s[46:47]
	s_waitcnt lgkmcnt(4)
	v_mfma_f32_16x16x32_bf16 v[56:59], v[158:161], v[178:181], v[56:59]
	v_mfma_f32_16x16x32_bf16 v[60:63], v[162:165], v[178:181], v[60:63]
	s_waitcnt lgkmcnt(3)
	v_mfma_f32_16x16x32_bf16 v[72:75], v[158:161], v[222:225], v[72:75]
	v_mfma_f32_16x16x32_bf16 v[76:79], v[162:165], v[222:225], v[76:79]
	s_waitcnt lgkmcnt(2)
	s_mov_b32 m0, s36
	v_mfma_f32_16x16x32_bf16 v[48:51], v[214:217], v[166:169], v[48:51]
	global_load_lds_dwordx4 v146, s[48:49]
	s_waitcnt lgkmcnt(1)
	v_mfma_f32_16x16x32_bf16 v[174:177], v[218:221], v[166:169], v[174:177]
	ds_read_b128 v[166:169], v28
	v_mfma_f32_16x16x32_bf16 v[64:67], v[214:217], v[178:181], v[64:67]
	v_mfma_f32_16x16x32_bf16 v[170:173], v[218:221], v[178:181], v[170:173]
	ds_read_b128 v[178:181], v29
	v_mfma_f32_16x16x32_bf16 v[80:83], v[214:217], v[222:225], v[80:83]
	v_mfma_f32_16x16x32_bf16 v[32:35], v[218:221], v[222:225], v[32:35]
	ds_read_b128 v[222:225], v30
	s_waitcnt lgkmcnt(3)
	v_mfma_f32_16x16x32_bf16 v[88:91], v[158:161], v[226:229], v[88:91]
	v_mfma_f32_16x16x32_bf16 v[92:95], v[162:165], v[226:229], v[92:95]
	v_mfma_f32_16x16x32_bf16 v[96:99], v[214:217], v[226:229], v[96:99]
	v_mfma_f32_16x16x32_bf16 v[36:39], v[218:221], v[226:229], v[36:39]
	ds_read_b128 v[226:229], v31
	s_waitcnt lgkmcnt(3)
	v_mfma_f32_16x16x32_bf16 v[104:107], v[158:161], v[166:169], v[104:107]
	v_mfma_f32_16x16x32_bf16 v[108:111], v[162:165], v[166:169], v[108:111]
	v_mfma_f32_16x16x32_bf16 v[112:115], v[214:217], v[166:169], v[112:115]
	v_mfma_f32_16x16x32_bf16 v[52:55], v[218:221], v[166:169], v[52:55]
	s_waitcnt lgkmcnt(2)
	v_mfma_f32_16x16x32_bf16 v[116:119], v[158:161], v[178:181], v[116:119]
	v_mfma_f32_16x16x32_bf16 v[120:123], v[162:165], v[178:181], v[120:123]
	v_mfma_f32_16x16x32_bf16 v[124:127], v[214:217], v[178:181], v[124:127]
	v_mfma_f32_16x16x32_bf16 v[68:71], v[218:221], v[178:181], v[68:71]
	s_waitcnt lgkmcnt(1)
	v_mfma_f32_16x16x32_bf16 v[128:131], v[158:161], v[222:225], v[128:131]
	v_mfma_f32_16x16x32_bf16 v[132:135], v[162:165], v[222:225], v[132:135]
	v_mfma_f32_16x16x32_bf16 v[136:139], v[214:217], v[222:225], v[136:139]
	v_mfma_f32_16x16x32_bf16 v[84:87], v[218:221], v[222:225], v[84:87]
	s_waitcnt lgkmcnt(0)
	v_mfma_f32_16x16x32_bf16 v[100:103], v[158:161], v[226:229], v[100:103]
	v_mfma_f32_16x16x32_bf16 v[140:143], v[162:165], v[226:229], v[140:143]
	v_mfma_f32_16x16x32_bf16 v[150:153], v[214:217], v[226:229], v[150:153]
	v_mfma_f32_16x16x32_bf16 v[154:157], v[218:221], v[226:229], v[154:157]
	s_add_u32 s46, s0, 0x580
	s_addc_u32 s47, s1, 0
	s_add_u32 s48, s14, 0x580
	s_waitcnt vmcnt(0)
	s_barrier
	s_addc_u32 s49, s15, 0
	ds_read_b128 v[158:161], v7 offset:32768
	ds_read_b128 v[162:165], v6
	ds_read_b128 v[166:169], v7 offset:34816
	ds_read_b128 v[178:181], v6 offset:2048
	ds_read_b128 v[214:217], v7 offset:36864
	ds_read_b128 v[218:221], v7 offset:38912
	ds_read_b128 v[222:225], v6 offset:4096
	ds_read_b128 v[226:229], v6 offset:6144
	s_waitcnt lgkmcnt(6)
	v_mfma_f32_16x16x32_bf16 v[40:43], v[158:161], v[162:165], v[40:43]
	s_waitcnt lgkmcnt(5)
	v_mfma_f32_16x16x32_bf16 v[44:47], v[166:169], v[162:165], v[44:47]
	s_waitcnt lgkmcnt(4)
	v_mfma_f32_16x16x32_bf16 v[56:59], v[158:161], v[178:181], v[56:59]
	s_mov_b32 m0, s38
	v_mfma_f32_16x16x32_bf16 v[60:63], v[166:169], v[178:181], v[60:63]
	global_load_lds_dwordx4 v0, s[46:47]
	s_waitcnt lgkmcnt(3)
	v_mfma_f32_16x16x32_bf16 v[48:51], v[214:217], v[162:165], v[48:51]
	v_mfma_f32_16x16x32_bf16 v[64:67], v[214:217], v[178:181], v[64:67]
	s_waitcnt lgkmcnt(2)
	v_mfma_f32_16x16x32_bf16 v[174:177], v[218:221], v[162:165], v[174:177]
	ds_read_b128 v[162:165], v6 offset:8192
	v_mfma_f32_16x16x32_bf16 v[170:173], v[218:221], v[178:181], v[170:173]
	ds_read_b128 v[178:181], v6 offset:10240
	s_waitcnt lgkmcnt(3)
	s_mov_b32 m0, s37
	v_mfma_f32_16x16x32_bf16 v[72:75], v[158:161], v[222:225], v[72:75]
	global_load_lds_dwordx4 v0, s[48:49]
	v_mfma_f32_16x16x32_bf16 v[76:79], v[166:169], v[222:225], v[76:79]
	v_mfma_f32_16x16x32_bf16 v[80:83], v[214:217], v[222:225], v[80:83]
	v_mfma_f32_16x16x32_bf16 v[32:35], v[218:221], v[222:225], v[32:35]
	ds_read_b128 v[222:225], v6 offset:12288
	s_waitcnt lgkmcnt(3)
	v_mfma_f32_16x16x32_bf16 v[88:91], v[158:161], v[226:229], v[88:91]
	s_mov_b32 m0, s39
	v_mfma_f32_16x16x32_bf16 v[92:95], v[166:169], v[226:229], v[92:95]
	global_load_lds_dwordx4 v2, s[46:47]
	v_mfma_f32_16x16x32_bf16 v[96:99], v[214:217], v[226:229], v[96:99]
	v_mfma_f32_16x16x32_bf16 v[36:39], v[218:221], v[226:229], v[36:39]
	ds_read_b128 v[226:229], v6 offset:14336
	s_waitcnt lgkmcnt(3)
	v_mfma_f32_16x16x32_bf16 v[104:107], v[158:161], v[162:165], v[104:107]
	s_waitcnt lgkmcnt(2)
	v_mfma_f32_16x16x32_bf16 v[116:119], v[158:161], v[178:181], v[116:119]
	s_waitcnt lgkmcnt(1)
	s_mov_b32 m0, s40
	v_mfma_f32_16x16x32_bf16 v[128:131], v[158:161], v[222:225], v[128:131]
	global_load_lds_dwordx4 v2, s[48:49]
	s_waitcnt lgkmcnt(0)
	v_mfma_f32_16x16x32_bf16 v[100:103], v[158:161], v[226:229], v[100:103]
	ds_read_b128 v[158:161], v7 offset:33792
	v_mfma_f32_16x16x32_bf16 v[108:111], v[166:169], v[162:165], v[108:111]
	v_mfma_f32_16x16x32_bf16 v[120:123], v[166:169], v[178:181], v[120:123]
	v_mfma_f32_16x16x32_bf16 v[132:135], v[166:169], v[222:225], v[132:135]
	s_mov_b32 m0, s41
	v_mfma_f32_16x16x32_bf16 v[140:143], v[166:169], v[226:229], v[140:143]
	global_load_lds_dwordx4 v4, s[46:47]
	ds_read_b128 v[166:169], v6 offset:1024
	v_mfma_f32_16x16x32_bf16 v[112:115], v[214:217], v[162:165], v[112:115]
	v_mfma_f32_16x16x32_bf16 v[52:55], v[218:221], v[162:165], v[52:55]
	ds_read_b128 v[162:165], v7 offset:35840
	v_mfma_f32_16x16x32_bf16 v[124:127], v[214:217], v[178:181], v[124:127]
	v_mfma_f32_16x16x32_bf16 v[68:71], v[218:221], v[178:181], v[68:71]
	ds_read_b128 v[178:181], v6 offset:3072
	s_mov_b32 m0, s42
	v_mfma_f32_16x16x32_bf16 v[136:139], v[214:217], v[222:225], v[136:139]
	global_load_lds_dwordx4 v4, s[48:49]
	v_mfma_f32_16x16x32_bf16 v[84:87], v[218:221], v[222:225], v[84:87]
	ds_read_b128 v[222:225], v6 offset:5120
	v_mfma_f32_16x16x32_bf16 v[150:153], v[214:217], v[226:229], v[150:153]
	ds_read_b128 v[214:217], v7 offset:37888
	v_mfma_f32_16x16x32_bf16 v[154:157], v[218:221], v[226:229], v[154:157]
	ds_read_b128 v[218:221], v7 offset:39936
	ds_read_b128 v[226:229], v6 offset:7168
	s_waitcnt lgkmcnt(6)
	v_mfma_f32_16x16x32_bf16 v[40:43], v[158:161], v[166:169], v[40:43]
	s_waitcnt lgkmcnt(5)
	s_mov_b32 m0, s43
	v_mfma_f32_16x16x32_bf16 v[44:47], v[162:165], v[166:169], v[44:47]
	global_load_lds_dwordx4 v146, s[46:47]
	s_waitcnt lgkmcnt(4)
	v_mfma_f32_16x16x32_bf16 v[56:59], v[158:161], v[178:181], v[56:59]
	v_mfma_f32_16x16x32_bf16 v[60:63], v[162:165], v[178:181], v[60:63]
	s_waitcnt lgkmcnt(3)
	v_mfma_f32_16x16x32_bf16 v[72:75], v[158:161], v[222:225], v[72:75]
	v_mfma_f32_16x16x32_bf16 v[76:79], v[162:165], v[222:225], v[76:79]
	s_waitcnt lgkmcnt(2)
	s_mov_b32 m0, s44
	v_mfma_f32_16x16x32_bf16 v[48:51], v[214:217], v[166:169], v[48:51]
	global_load_lds_dwordx4 v146, s[48:49]
	s_waitcnt lgkmcnt(1)
	v_mfma_f32_16x16x32_bf16 v[174:177], v[218:221], v[166:169], v[174:177]
	ds_read_b128 v[166:169], v6 offset:9216
	v_mfma_f32_16x16x32_bf16 v[64:67], v[214:217], v[178:181], v[64:67]
	v_mfma_f32_16x16x32_bf16 v[170:173], v[218:221], v[178:181], v[170:173]
	ds_read_b128 v[178:181], v6 offset:11264
	v_mfma_f32_16x16x32_bf16 v[80:83], v[214:217], v[222:225], v[80:83]
	v_mfma_f32_16x16x32_bf16 v[32:35], v[218:221], v[222:225], v[32:35]
	ds_read_b128 v[222:225], v6 offset:13312
	s_waitcnt lgkmcnt(3)
	v_mfma_f32_16x16x32_bf16 v[88:91], v[158:161], v[226:229], v[88:91]
	v_mfma_f32_16x16x32_bf16 v[92:95], v[162:165], v[226:229], v[92:95]
	v_mfma_f32_16x16x32_bf16 v[96:99], v[214:217], v[226:229], v[96:99]
	v_mfma_f32_16x16x32_bf16 v[36:39], v[218:221], v[226:229], v[36:39]
	ds_read_b128 v[226:229], v6 offset:15360
	s_waitcnt lgkmcnt(3)
	v_mfma_f32_16x16x32_bf16 v[104:107], v[158:161], v[166:169], v[104:107]
	v_mfma_f32_16x16x32_bf16 v[108:111], v[162:165], v[166:169], v[108:111]
	v_mfma_f32_16x16x32_bf16 v[112:115], v[214:217], v[166:169], v[112:115]
	v_mfma_f32_16x16x32_bf16 v[52:55], v[218:221], v[166:169], v[52:55]
	s_waitcnt lgkmcnt(2)
	v_mfma_f32_16x16x32_bf16 v[116:119], v[158:161], v[178:181], v[116:119]
	v_mfma_f32_16x16x32_bf16 v[120:123], v[162:165], v[178:181], v[120:123]
	v_mfma_f32_16x16x32_bf16 v[124:127], v[214:217], v[178:181], v[124:127]
	v_mfma_f32_16x16x32_bf16 v[68:71], v[218:221], v[178:181], v[68:71]
	s_waitcnt lgkmcnt(1)
	v_mfma_f32_16x16x32_bf16 v[128:131], v[158:161], v[222:225], v[128:131]
	v_mfma_f32_16x16x32_bf16 v[132:135], v[162:165], v[222:225], v[132:135]
	v_mfma_f32_16x16x32_bf16 v[136:139], v[214:217], v[222:225], v[136:139]
	v_mfma_f32_16x16x32_bf16 v[84:87], v[218:221], v[222:225], v[84:87]
	s_waitcnt lgkmcnt(0)
	v_mfma_f32_16x16x32_bf16 v[100:103], v[158:161], v[226:229], v[100:103]
	v_mfma_f32_16x16x32_bf16 v[140:143], v[162:165], v[226:229], v[140:143]
	v_mfma_f32_16x16x32_bf16 v[150:153], v[214:217], v[226:229], v[150:153]
	v_mfma_f32_16x16x32_bf16 v[154:157], v[218:221], v[226:229], v[154:157]
	s_add_u32 s46, s0, 0x600
	s_addc_u32 s47, s1, 0
	s_add_u32 s48, s14, 0x600
	s_waitcnt vmcnt(0)
	s_barrier
	s_addc_u32 s49, s15, 0
	ds_read_b128 v[158:161], v8
	ds_read_b128 v[162:165], v12
	ds_read_b128 v[166:169], v9
	ds_read_b128 v[178:181], v13
	ds_read_b128 v[214:217], v11
	ds_read_b128 v[218:221], v10
	ds_read_b128 v[222:225], v14
	ds_read_b128 v[226:229], v15
	s_waitcnt lgkmcnt(6)
	v_mfma_f32_16x16x32_bf16 v[40:43], v[158:161], v[162:165], v[40:43]
	s_waitcnt lgkmcnt(5)
	v_mfma_f32_16x16x32_bf16 v[44:47], v[166:169], v[162:165], v[44:47]
	s_waitcnt lgkmcnt(4)
	v_mfma_f32_16x16x32_bf16 v[56:59], v[158:161], v[178:181], v[56:59]
	s_mov_b32 m0, s27
	v_mfma_f32_16x16x32_bf16 v[60:63], v[166:169], v[178:181], v[60:63]
	global_load_lds_dwordx4 v0, s[46:47]
	s_waitcnt lgkmcnt(3)
	v_mfma_f32_16x16x32_bf16 v[48:51], v[214:217], v[162:165], v[48:51]
	v_mfma_f32_16x16x32_bf16 v[64:67], v[214:217], v[178:181], v[64:67]
	s_waitcnt lgkmcnt(2)
	v_mfma_f32_16x16x32_bf16 v[174:177], v[218:221], v[162:165], v[174:177]
	ds_read_b128 v[162:165], v16
	v_mfma_f32_16x16x32_bf16 v[170:173], v[218:221], v[178:181], v[170:173]
	ds_read_b128 v[178:181], v17
	s_waitcnt lgkmcnt(3)
	s_mov_b32 m0, s28
	v_mfma_f32_16x16x32_bf16 v[72:75], v[158:161], v[222:225], v[72:75]
	global_load_lds_dwordx4 v0, s[48:49]
	v_mfma_f32_16x16x32_bf16 v[76:79], v[166:169], v[222:225], v[76:79]
	v_mfma_f32_16x16x32_bf16 v[80:83], v[214:217], v[222:225], v[80:83]
	v_mfma_f32_16x16x32_bf16 v[32:35], v[218:221], v[222:225], v[32:35]
	ds_read_b128 v[222:225], v18
	s_waitcnt lgkmcnt(3)
	v_mfma_f32_16x16x32_bf16 v[88:91], v[158:161], v[226:229], v[88:91]
	s_mov_b32 m0, s29
	v_mfma_f32_16x16x32_bf16 v[92:95], v[166:169], v[226:229], v[92:95]
	global_load_lds_dwordx4 v2, s[46:47]
	v_mfma_f32_16x16x32_bf16 v[96:99], v[214:217], v[226:229], v[96:99]
	v_mfma_f32_16x16x32_bf16 v[36:39], v[218:221], v[226:229], v[36:39]
	ds_read_b128 v[226:229], v19
	s_waitcnt lgkmcnt(3)
	v_mfma_f32_16x16x32_bf16 v[104:107], v[158:161], v[162:165], v[104:107]
	s_waitcnt lgkmcnt(2)
	v_mfma_f32_16x16x32_bf16 v[116:119], v[158:161], v[178:181], v[116:119]
	s_waitcnt lgkmcnt(1)
	s_mov_b32 m0, s30
	v_mfma_f32_16x16x32_bf16 v[128:131], v[158:161], v[222:225], v[128:131]
	global_load_lds_dwordx4 v2, s[48:49]
	s_waitcnt lgkmcnt(0)
	v_mfma_f32_16x16x32_bf16 v[100:103], v[158:161], v[226:229], v[100:103]
	ds_read_b128 v[158:161], v20
	v_mfma_f32_16x16x32_bf16 v[108:111], v[166:169], v[162:165], v[108:111]
	v_mfma_f32_16x16x32_bf16 v[120:123], v[166:169], v[178:181], v[120:123]
	v_mfma_f32_16x16x32_bf16 v[132:135], v[166:169], v[222:225], v[132:135]
	s_mov_b32 m0, s31
	v_mfma_f32_16x16x32_bf16 v[140:143], v[166:169], v[226:229], v[140:143]
	global_load_lds_dwordx4 v4, s[46:47]
	ds_read_b128 v[166:169], v24
	v_mfma_f32_16x16x32_bf16 v[112:115], v[214:217], v[162:165], v[112:115]
	v_mfma_f32_16x16x32_bf16 v[52:55], v[218:221], v[162:165], v[52:55]
	ds_read_b128 v[162:165], v21
	v_mfma_f32_16x16x32_bf16 v[124:127], v[214:217], v[178:181], v[124:127]
	v_mfma_f32_16x16x32_bf16 v[68:71], v[218:221], v[178:181], v[68:71]
	ds_read_b128 v[178:181], v25
	s_mov_b32 m0, s34
	v_mfma_f32_16x16x32_bf16 v[136:139], v[214:217], v[222:225], v[136:139]
	global_load_lds_dwordx4 v4, s[48:49]
	v_mfma_f32_16x16x32_bf16 v[84:87], v[218:221], v[222:225], v[84:87]
	ds_read_b128 v[222:225], v26
	v_mfma_f32_16x16x32_bf16 v[150:153], v[214:217], v[226:229], v[150:153]
	ds_read_b128 v[214:217], v23
	v_mfma_f32_16x16x32_bf16 v[154:157], v[218:221], v[226:229], v[154:157]
	ds_read_b128 v[218:221], v22
	ds_read_b128 v[226:229], v27
	s_waitcnt lgkmcnt(6)
	v_mfma_f32_16x16x32_bf16 v[40:43], v[158:161], v[166:169], v[40:43]
	s_waitcnt lgkmcnt(5)
	s_mov_b32 m0, s35
	v_mfma_f32_16x16x32_bf16 v[44:47], v[162:165], v[166:169], v[44:47]
	global_load_lds_dwordx4 v146, s[46:47]
	s_waitcnt lgkmcnt(4)
	v_mfma_f32_16x16x32_bf16 v[56:59], v[158:161], v[178:181], v[56:59]
	v_mfma_f32_16x16x32_bf16 v[60:63], v[162:165], v[178:181], v[60:63]
	s_waitcnt lgkmcnt(3)
	v_mfma_f32_16x16x32_bf16 v[72:75], v[158:161], v[222:225], v[72:75]
	v_mfma_f32_16x16x32_bf16 v[76:79], v[162:165], v[222:225], v[76:79]
	s_waitcnt lgkmcnt(2)
	s_mov_b32 m0, s36
	v_mfma_f32_16x16x32_bf16 v[48:51], v[214:217], v[166:169], v[48:51]
	global_load_lds_dwordx4 v146, s[48:49]
	s_waitcnt lgkmcnt(1)
	v_mfma_f32_16x16x32_bf16 v[174:177], v[218:221], v[166:169], v[174:177]
	ds_read_b128 v[166:169], v28
	v_mfma_f32_16x16x32_bf16 v[64:67], v[214:217], v[178:181], v[64:67]
	v_mfma_f32_16x16x32_bf16 v[170:173], v[218:221], v[178:181], v[170:173]
	ds_read_b128 v[178:181], v29
	v_mfma_f32_16x16x32_bf16 v[80:83], v[214:217], v[222:225], v[80:83]
	v_mfma_f32_16x16x32_bf16 v[32:35], v[218:221], v[222:225], v[32:35]
	ds_read_b128 v[222:225], v30
	s_waitcnt lgkmcnt(3)
	v_mfma_f32_16x16x32_bf16 v[88:91], v[158:161], v[226:229], v[88:91]
	v_mfma_f32_16x16x32_bf16 v[92:95], v[162:165], v[226:229], v[92:95]
	v_mfma_f32_16x16x32_bf16 v[96:99], v[214:217], v[226:229], v[96:99]
	v_mfma_f32_16x16x32_bf16 v[36:39], v[218:221], v[226:229], v[36:39]
	ds_read_b128 v[226:229], v31
	s_waitcnt lgkmcnt(3)
	v_mfma_f32_16x16x32_bf16 v[104:107], v[158:161], v[166:169], v[104:107]
	v_mfma_f32_16x16x32_bf16 v[108:111], v[162:165], v[166:169], v[108:111]
	v_mfma_f32_16x16x32_bf16 v[112:115], v[214:217], v[166:169], v[112:115]
	v_mfma_f32_16x16x32_bf16 v[52:55], v[218:221], v[166:169], v[52:55]
	s_waitcnt lgkmcnt(2)
	v_mfma_f32_16x16x32_bf16 v[116:119], v[158:161], v[178:181], v[116:119]
	v_mfma_f32_16x16x32_bf16 v[120:123], v[162:165], v[178:181], v[120:123]
	v_mfma_f32_16x16x32_bf16 v[124:127], v[214:217], v[178:181], v[124:127]
	v_mfma_f32_16x16x32_bf16 v[68:71], v[218:221], v[178:181], v[68:71]
	s_waitcnt lgkmcnt(1)
	v_mfma_f32_16x16x32_bf16 v[128:131], v[158:161], v[222:225], v[128:131]
	v_mfma_f32_16x16x32_bf16 v[132:135], v[162:165], v[222:225], v[132:135]
	v_mfma_f32_16x16x32_bf16 v[136:139], v[214:217], v[222:225], v[136:139]
	v_mfma_f32_16x16x32_bf16 v[84:87], v[218:221], v[222:225], v[84:87]
	s_waitcnt lgkmcnt(0)
	v_mfma_f32_16x16x32_bf16 v[100:103], v[158:161], v[226:229], v[100:103]
	v_mfma_f32_16x16x32_bf16 v[140:143], v[162:165], v[226:229], v[140:143]
	v_mfma_f32_16x16x32_bf16 v[150:153], v[214:217], v[226:229], v[150:153]
	v_mfma_f32_16x16x32_bf16 v[154:157], v[218:221], v[226:229], v[154:157]
	s_add_u32 s46, s0, 0x680
	s_addc_u32 s47, s1, 0
	s_add_u32 s48, s14, 0x680
	s_waitcnt vmcnt(0)
	s_barrier
	s_addc_u32 s49, s15, 0
	ds_read_b128 v[158:161], v7 offset:32768
	ds_read_b128 v[162:165], v6
	ds_read_b128 v[166:169], v7 offset:34816
	ds_read_b128 v[178:181], v6 offset:2048
	ds_read_b128 v[214:217], v7 offset:36864
	ds_read_b128 v[218:221], v7 offset:38912
	ds_read_b128 v[222:225], v6 offset:4096
	ds_read_b128 v[226:229], v6 offset:6144
	s_waitcnt lgkmcnt(6)
	v_mfma_f32_16x16x32_bf16 v[40:43], v[158:161], v[162:165], v[40:43]
	s_waitcnt lgkmcnt(5)
	v_mfma_f32_16x16x32_bf16 v[44:47], v[166:169], v[162:165], v[44:47]
	s_waitcnt lgkmcnt(4)
	v_mfma_f32_16x16x32_bf16 v[56:59], v[158:161], v[178:181], v[56:59]
	s_mov_b32 m0, s38
	v_mfma_f32_16x16x32_bf16 v[60:63], v[166:169], v[178:181], v[60:63]
	global_load_lds_dwordx4 v0, s[46:47]
	s_waitcnt lgkmcnt(3)
	v_mfma_f32_16x16x32_bf16 v[48:51], v[214:217], v[162:165], v[48:51]
	v_mfma_f32_16x16x32_bf16 v[64:67], v[214:217], v[178:181], v[64:67]
	s_waitcnt lgkmcnt(2)
	v_mfma_f32_16x16x32_bf16 v[174:177], v[218:221], v[162:165], v[174:177]
	ds_read_b128 v[162:165], v6 offset:8192
	v_mfma_f32_16x16x32_bf16 v[170:173], v[218:221], v[178:181], v[170:173]
	ds_read_b128 v[178:181], v6 offset:10240
	s_waitcnt lgkmcnt(3)
	s_mov_b32 m0, s37
	v_mfma_f32_16x16x32_bf16 v[72:75], v[158:161], v[222:225], v[72:75]
	global_load_lds_dwordx4 v0, s[48:49]
	v_mfma_f32_16x16x32_bf16 v[76:79], v[166:169], v[222:225], v[76:79]
	v_mfma_f32_16x16x32_bf16 v[80:83], v[214:217], v[222:225], v[80:83]
	v_mfma_f32_16x16x32_bf16 v[32:35], v[218:221], v[222:225], v[32:35]
	ds_read_b128 v[222:225], v6 offset:12288
	s_waitcnt lgkmcnt(3)
	v_mfma_f32_16x16x32_bf16 v[88:91], v[158:161], v[226:229], v[88:91]
	s_mov_b32 m0, s39
	v_mfma_f32_16x16x32_bf16 v[92:95], v[166:169], v[226:229], v[92:95]
	global_load_lds_dwordx4 v2, s[46:47]
	v_mfma_f32_16x16x32_bf16 v[96:99], v[214:217], v[226:229], v[96:99]
	v_mfma_f32_16x16x32_bf16 v[36:39], v[218:221], v[226:229], v[36:39]
	ds_read_b128 v[226:229], v6 offset:14336
	s_waitcnt lgkmcnt(3)
	v_mfma_f32_16x16x32_bf16 v[104:107], v[158:161], v[162:165], v[104:107]
	s_waitcnt lgkmcnt(2)
	v_mfma_f32_16x16x32_bf16 v[116:119], v[158:161], v[178:181], v[116:119]
	s_waitcnt lgkmcnt(1)
	s_mov_b32 m0, s40
	v_mfma_f32_16x16x32_bf16 v[128:131], v[158:161], v[222:225], v[128:131]
	global_load_lds_dwordx4 v2, s[48:49]
	s_waitcnt lgkmcnt(0)
	v_mfma_f32_16x16x32_bf16 v[100:103], v[158:161], v[226:229], v[100:103]
	ds_read_b128 v[158:161], v7 offset:33792
	v_mfma_f32_16x16x32_bf16 v[108:111], v[166:169], v[162:165], v[108:111]
	v_mfma_f32_16x16x32_bf16 v[120:123], v[166:169], v[178:181], v[120:123]
	v_mfma_f32_16x16x32_bf16 v[132:135], v[166:169], v[222:225], v[132:135]
	s_mov_b32 m0, s41
	v_mfma_f32_16x16x32_bf16 v[140:143], v[166:169], v[226:229], v[140:143]
	global_load_lds_dwordx4 v4, s[46:47]
	ds_read_b128 v[166:169], v6 offset:1024
	v_mfma_f32_16x16x32_bf16 v[112:115], v[214:217], v[162:165], v[112:115]
	v_mfma_f32_16x16x32_bf16 v[52:55], v[218:221], v[162:165], v[52:55]
	ds_read_b128 v[162:165], v7 offset:35840
	v_mfma_f32_16x16x32_bf16 v[124:127], v[214:217], v[178:181], v[124:127]
	v_mfma_f32_16x16x32_bf16 v[68:71], v[218:221], v[178:181], v[68:71]
	ds_read_b128 v[178:181], v6 offset:3072
	s_mov_b32 m0, s42
	v_mfma_f32_16x16x32_bf16 v[136:139], v[214:217], v[222:225], v[136:139]
	global_load_lds_dwordx4 v4, s[48:49]
	v_mfma_f32_16x16x32_bf16 v[84:87], v[218:221], v[222:225], v[84:87]
	ds_read_b128 v[222:225], v6 offset:5120
	v_mfma_f32_16x16x32_bf16 v[150:153], v[214:217], v[226:229], v[150:153]
	ds_read_b128 v[214:217], v7 offset:37888
	v_mfma_f32_16x16x32_bf16 v[154:157], v[218:221], v[226:229], v[154:157]
	ds_read_b128 v[218:221], v7 offset:39936
	ds_read_b128 v[226:229], v6 offset:7168
	s_waitcnt lgkmcnt(6)
	v_mfma_f32_16x16x32_bf16 v[40:43], v[158:161], v[166:169], v[40:43]
	s_waitcnt lgkmcnt(5)
	s_mov_b32 m0, s43
	v_mfma_f32_16x16x32_bf16 v[44:47], v[162:165], v[166:169], v[44:47]
	global_load_lds_dwordx4 v146, s[46:47]
	s_waitcnt lgkmcnt(4)
	v_mfma_f32_16x16x32_bf16 v[56:59], v[158:161], v[178:181], v[56:59]
	v_mfma_f32_16x16x32_bf16 v[60:63], v[162:165], v[178:181], v[60:63]
	s_waitcnt lgkmcnt(3)
	v_mfma_f32_16x16x32_bf16 v[72:75], v[158:161], v[222:225], v[72:75]
	v_mfma_f32_16x16x32_bf16 v[76:79], v[162:165], v[222:225], v[76:79]
	s_waitcnt lgkmcnt(2)
	s_mov_b32 m0, s44
	v_mfma_f32_16x16x32_bf16 v[48:51], v[214:217], v[166:169], v[48:51]
	global_load_lds_dwordx4 v146, s[48:49]
	s_waitcnt lgkmcnt(1)
	v_mfma_f32_16x16x32_bf16 v[174:177], v[218:221], v[166:169], v[174:177]
	ds_read_b128 v[166:169], v6 offset:9216
	v_mfma_f32_16x16x32_bf16 v[64:67], v[214:217], v[178:181], v[64:67]
	v_mfma_f32_16x16x32_bf16 v[170:173], v[218:221], v[178:181], v[170:173]
	ds_read_b128 v[178:181], v6 offset:11264
	v_mfma_f32_16x16x32_bf16 v[80:83], v[214:217], v[222:225], v[80:83]
	v_mfma_f32_16x16x32_bf16 v[32:35], v[218:221], v[222:225], v[32:35]
	ds_read_b128 v[222:225], v6 offset:13312
	s_waitcnt lgkmcnt(3)
	v_mfma_f32_16x16x32_bf16 v[88:91], v[158:161], v[226:229], v[88:91]
	v_mfma_f32_16x16x32_bf16 v[92:95], v[162:165], v[226:229], v[92:95]
	v_mfma_f32_16x16x32_bf16 v[96:99], v[214:217], v[226:229], v[96:99]
	v_mfma_f32_16x16x32_bf16 v[36:39], v[218:221], v[226:229], v[36:39]
	ds_read_b128 v[226:229], v6 offset:15360
	s_waitcnt lgkmcnt(3)
	v_mfma_f32_16x16x32_bf16 v[104:107], v[158:161], v[166:169], v[104:107]
	v_mfma_f32_16x16x32_bf16 v[108:111], v[162:165], v[166:169], v[108:111]
	v_mfma_f32_16x16x32_bf16 v[112:115], v[214:217], v[166:169], v[112:115]
	v_mfma_f32_16x16x32_bf16 v[52:55], v[218:221], v[166:169], v[52:55]
	s_waitcnt lgkmcnt(2)
	v_mfma_f32_16x16x32_bf16 v[116:119], v[158:161], v[178:181], v[116:119]
	v_mfma_f32_16x16x32_bf16 v[120:123], v[162:165], v[178:181], v[120:123]
	v_mfma_f32_16x16x32_bf16 v[124:127], v[214:217], v[178:181], v[124:127]
	v_mfma_f32_16x16x32_bf16 v[68:71], v[218:221], v[178:181], v[68:71]
	s_waitcnt lgkmcnt(1)
	v_mfma_f32_16x16x32_bf16 v[128:131], v[158:161], v[222:225], v[128:131]
	v_mfma_f32_16x16x32_bf16 v[132:135], v[162:165], v[222:225], v[132:135]
	v_mfma_f32_16x16x32_bf16 v[136:139], v[214:217], v[222:225], v[136:139]
	v_mfma_f32_16x16x32_bf16 v[84:87], v[218:221], v[222:225], v[84:87]
	s_waitcnt lgkmcnt(0)
	v_mfma_f32_16x16x32_bf16 v[100:103], v[158:161], v[226:229], v[100:103]
	v_mfma_f32_16x16x32_bf16 v[140:143], v[162:165], v[226:229], v[140:143]
	v_mfma_f32_16x16x32_bf16 v[150:153], v[214:217], v[226:229], v[150:153]
	v_mfma_f32_16x16x32_bf16 v[154:157], v[218:221], v[226:229], v[154:157]
	s_add_u32 s46, s0, 0x700
	s_addc_u32 s47, s1, 0
	s_add_u32 s48, s14, 0x700
	s_waitcnt vmcnt(0)
	s_barrier
	s_addc_u32 s49, s15, 0
	ds_read_b128 v[158:161], v8
	ds_read_b128 v[162:165], v12
	ds_read_b128 v[166:169], v9
	ds_read_b128 v[178:181], v13
	ds_read_b128 v[214:217], v11
	ds_read_b128 v[218:221], v10
	ds_read_b128 v[222:225], v14
	ds_read_b128 v[226:229], v15
	s_waitcnt lgkmcnt(6)
	v_mfma_f32_16x16x32_bf16 v[40:43], v[158:161], v[162:165], v[40:43]
	s_waitcnt lgkmcnt(5)
	v_mfma_f32_16x16x32_bf16 v[44:47], v[166:169], v[162:165], v[44:47]
	s_waitcnt lgkmcnt(4)
	v_mfma_f32_16x16x32_bf16 v[56:59], v[158:161], v[178:181], v[56:59]
	s_mov_b32 m0, s27
	v_mfma_f32_16x16x32_bf16 v[60:63], v[166:169], v[178:181], v[60:63]
	global_load_lds_dwordx4 v0, s[46:47]
	s_waitcnt lgkmcnt(3)
	v_mfma_f32_16x16x32_bf16 v[48:51], v[214:217], v[162:165], v[48:51]
	v_mfma_f32_16x16x32_bf16 v[64:67], v[214:217], v[178:181], v[64:67]
	s_waitcnt lgkmcnt(2)
	v_mfma_f32_16x16x32_bf16 v[174:177], v[218:221], v[162:165], v[174:177]
	ds_read_b128 v[162:165], v16
	v_mfma_f32_16x16x32_bf16 v[170:173], v[218:221], v[178:181], v[170:173]
	ds_read_b128 v[178:181], v17
	s_waitcnt lgkmcnt(3)
	s_mov_b32 m0, s28
	v_mfma_f32_16x16x32_bf16 v[72:75], v[158:161], v[222:225], v[72:75]
	global_load_lds_dwordx4 v0, s[48:49]
	v_mfma_f32_16x16x32_bf16 v[76:79], v[166:169], v[222:225], v[76:79]
	v_mfma_f32_16x16x32_bf16 v[80:83], v[214:217], v[222:225], v[80:83]
	v_mfma_f32_16x16x32_bf16 v[32:35], v[218:221], v[222:225], v[32:35]
	ds_read_b128 v[222:225], v18
	s_waitcnt lgkmcnt(3)
	v_mfma_f32_16x16x32_bf16 v[88:91], v[158:161], v[226:229], v[88:91]
	s_mov_b32 m0, s29
	v_mfma_f32_16x16x32_bf16 v[92:95], v[166:169], v[226:229], v[92:95]
	global_load_lds_dwordx4 v2, s[46:47]
	v_mfma_f32_16x16x32_bf16 v[96:99], v[214:217], v[226:229], v[96:99]
	v_mfma_f32_16x16x32_bf16 v[36:39], v[218:221], v[226:229], v[36:39]
	ds_read_b128 v[226:229], v19
	s_waitcnt lgkmcnt(3)
	v_mfma_f32_16x16x32_bf16 v[104:107], v[158:161], v[162:165], v[104:107]
	s_waitcnt lgkmcnt(2)
	v_mfma_f32_16x16x32_bf16 v[116:119], v[158:161], v[178:181], v[116:119]
	s_waitcnt lgkmcnt(1)
	s_mov_b32 m0, s30
	v_mfma_f32_16x16x32_bf16 v[128:131], v[158:161], v[222:225], v[128:131]
	global_load_lds_dwordx4 v2, s[48:49]
	s_waitcnt lgkmcnt(0)
	v_mfma_f32_16x16x32_bf16 v[100:103], v[158:161], v[226:229], v[100:103]
	ds_read_b128 v[158:161], v20
	v_mfma_f32_16x16x32_bf16 v[108:111], v[166:169], v[162:165], v[108:111]
	v_mfma_f32_16x16x32_bf16 v[120:123], v[166:169], v[178:181], v[120:123]
	v_mfma_f32_16x16x32_bf16 v[132:135], v[166:169], v[222:225], v[132:135]
	s_mov_b32 m0, s31
	v_mfma_f32_16x16x32_bf16 v[140:143], v[166:169], v[226:229], v[140:143]
	global_load_lds_dwordx4 v4, s[46:47]
	ds_read_b128 v[166:169], v24
	v_mfma_f32_16x16x32_bf16 v[112:115], v[214:217], v[162:165], v[112:115]
	v_mfma_f32_16x16x32_bf16 v[52:55], v[218:221], v[162:165], v[52:55]
	ds_read_b128 v[162:165], v21
	v_mfma_f32_16x16x32_bf16 v[124:127], v[214:217], v[178:181], v[124:127]
	v_mfma_f32_16x16x32_bf16 v[68:71], v[218:221], v[178:181], v[68:71]
	ds_read_b128 v[178:181], v25
	s_mov_b32 m0, s34
	v_mfma_f32_16x16x32_bf16 v[136:139], v[214:217], v[222:225], v[136:139]
	global_load_lds_dwordx4 v4, s[48:49]
	v_mfma_f32_16x16x32_bf16 v[84:87], v[218:221], v[222:225], v[84:87]
	ds_read_b128 v[222:225], v26
	v_mfma_f32_16x16x32_bf16 v[150:153], v[214:217], v[226:229], v[150:153]
	ds_read_b128 v[214:217], v23
	v_mfma_f32_16x16x32_bf16 v[154:157], v[218:221], v[226:229], v[154:157]
	ds_read_b128 v[218:221], v22
	ds_read_b128 v[226:229], v27
	s_waitcnt lgkmcnt(6)
	v_mfma_f32_16x16x32_bf16 v[40:43], v[158:161], v[166:169], v[40:43]
	s_waitcnt lgkmcnt(5)
	s_mov_b32 m0, s35
	v_mfma_f32_16x16x32_bf16 v[44:47], v[162:165], v[166:169], v[44:47]
	global_load_lds_dwordx4 v146, s[46:47]
	s_waitcnt lgkmcnt(4)
	v_mfma_f32_16x16x32_bf16 v[56:59], v[158:161], v[178:181], v[56:59]
	v_mfma_f32_16x16x32_bf16 v[60:63], v[162:165], v[178:181], v[60:63]
	s_waitcnt lgkmcnt(3)
	v_mfma_f32_16x16x32_bf16 v[72:75], v[158:161], v[222:225], v[72:75]
	v_mfma_f32_16x16x32_bf16 v[76:79], v[162:165], v[222:225], v[76:79]
	s_waitcnt lgkmcnt(2)
	s_mov_b32 m0, s36
	v_mfma_f32_16x16x32_bf16 v[48:51], v[214:217], v[166:169], v[48:51]
	global_load_lds_dwordx4 v146, s[48:49]
	s_waitcnt lgkmcnt(1)
	v_mfma_f32_16x16x32_bf16 v[174:177], v[218:221], v[166:169], v[174:177]
	ds_read_b128 v[166:169], v28
	v_mfma_f32_16x16x32_bf16 v[64:67], v[214:217], v[178:181], v[64:67]
	v_mfma_f32_16x16x32_bf16 v[170:173], v[218:221], v[178:181], v[170:173]
	ds_read_b128 v[178:181], v29
	v_mfma_f32_16x16x32_bf16 v[80:83], v[214:217], v[222:225], v[80:83]
	v_mfma_f32_16x16x32_bf16 v[32:35], v[218:221], v[222:225], v[32:35]
	ds_read_b128 v[222:225], v30
	s_waitcnt lgkmcnt(3)
	v_mfma_f32_16x16x32_bf16 v[88:91], v[158:161], v[226:229], v[88:91]
	v_mfma_f32_16x16x32_bf16 v[92:95], v[162:165], v[226:229], v[92:95]
	v_mfma_f32_16x16x32_bf16 v[96:99], v[214:217], v[226:229], v[96:99]
	v_mfma_f32_16x16x32_bf16 v[36:39], v[218:221], v[226:229], v[36:39]
	ds_read_b128 v[226:229], v31
	s_waitcnt lgkmcnt(3)
	v_mfma_f32_16x16x32_bf16 v[104:107], v[158:161], v[166:169], v[104:107]
	v_mfma_f32_16x16x32_bf16 v[108:111], v[162:165], v[166:169], v[108:111]
	v_mfma_f32_16x16x32_bf16 v[112:115], v[214:217], v[166:169], v[112:115]
	v_mfma_f32_16x16x32_bf16 v[52:55], v[218:221], v[166:169], v[52:55]
	s_waitcnt lgkmcnt(2)
	v_mfma_f32_16x16x32_bf16 v[116:119], v[158:161], v[178:181], v[116:119]
	v_mfma_f32_16x16x32_bf16 v[120:123], v[162:165], v[178:181], v[120:123]
	v_mfma_f32_16x16x32_bf16 v[124:127], v[214:217], v[178:181], v[124:127]
	v_mfma_f32_16x16x32_bf16 v[68:71], v[218:221], v[178:181], v[68:71]
	s_waitcnt lgkmcnt(1)
	v_mfma_f32_16x16x32_bf16 v[128:131], v[158:161], v[222:225], v[128:131]
	v_mfma_f32_16x16x32_bf16 v[132:135], v[162:165], v[222:225], v[132:135]
	v_mfma_f32_16x16x32_bf16 v[136:139], v[214:217], v[222:225], v[136:139]
	v_mfma_f32_16x16x32_bf16 v[84:87], v[218:221], v[222:225], v[84:87]
	s_waitcnt lgkmcnt(0)
	v_mfma_f32_16x16x32_bf16 v[100:103], v[158:161], v[226:229], v[100:103]
	v_mfma_f32_16x16x32_bf16 v[140:143], v[162:165], v[226:229], v[140:143]
	v_mfma_f32_16x16x32_bf16 v[150:153], v[214:217], v[226:229], v[150:153]
	v_mfma_f32_16x16x32_bf16 v[154:157], v[218:221], v[226:229], v[154:157]
	s_add_u32 s46, s0, 0x780
	s_addc_u32 s47, s1, 0
	s_add_u32 s48, s14, 0x780
	s_waitcnt vmcnt(0)
	s_barrier
	s_addc_u32 s49, s15, 0
	ds_read_b128 v[158:161], v7 offset:32768
	ds_read_b128 v[162:165], v6
	ds_read_b128 v[166:169], v7 offset:34816
	ds_read_b128 v[178:181], v6 offset:2048
	ds_read_b128 v[214:217], v7 offset:36864
	ds_read_b128 v[218:221], v7 offset:38912
	ds_read_b128 v[222:225], v6 offset:4096
	ds_read_b128 v[226:229], v6 offset:6144
	s_waitcnt lgkmcnt(6)
	v_mfma_f32_16x16x32_bf16 v[40:43], v[158:161], v[162:165], v[40:43]
	s_waitcnt lgkmcnt(5)
	v_mfma_f32_16x16x32_bf16 v[44:47], v[166:169], v[162:165], v[44:47]
	s_waitcnt lgkmcnt(4)
	v_mfma_f32_16x16x32_bf16 v[56:59], v[158:161], v[178:181], v[56:59]
	s_mov_b32 m0, s38
	v_mfma_f32_16x16x32_bf16 v[60:63], v[166:169], v[178:181], v[60:63]
	global_load_lds_dwordx4 v0, s[46:47]
	s_waitcnt lgkmcnt(3)
	v_mfma_f32_16x16x32_bf16 v[48:51], v[214:217], v[162:165], v[48:51]
	v_mfma_f32_16x16x32_bf16 v[64:67], v[214:217], v[178:181], v[64:67]
	s_waitcnt lgkmcnt(2)
	v_mfma_f32_16x16x32_bf16 v[174:177], v[218:221], v[162:165], v[174:177]
	ds_read_b128 v[162:165], v6 offset:8192
	v_mfma_f32_16x16x32_bf16 v[170:173], v[218:221], v[178:181], v[170:173]
	ds_read_b128 v[178:181], v6 offset:10240
	s_waitcnt lgkmcnt(3)
	s_mov_b32 m0, s37
	v_mfma_f32_16x16x32_bf16 v[72:75], v[158:161], v[222:225], v[72:75]
	global_load_lds_dwordx4 v0, s[48:49]
	v_mfma_f32_16x16x32_bf16 v[76:79], v[166:169], v[222:225], v[76:79]
	v_mfma_f32_16x16x32_bf16 v[80:83], v[214:217], v[222:225], v[80:83]
	v_mfma_f32_16x16x32_bf16 v[32:35], v[218:221], v[222:225], v[32:35]
	ds_read_b128 v[222:225], v6 offset:12288
	s_waitcnt lgkmcnt(3)
	v_mfma_f32_16x16x32_bf16 v[88:91], v[158:161], v[226:229], v[88:91]
	s_mov_b32 m0, s39
	v_mfma_f32_16x16x32_bf16 v[92:95], v[166:169], v[226:229], v[92:95]
	global_load_lds_dwordx4 v2, s[46:47]
	v_mfma_f32_16x16x32_bf16 v[96:99], v[214:217], v[226:229], v[96:99]
	v_mfma_f32_16x16x32_bf16 v[36:39], v[218:221], v[226:229], v[36:39]
	ds_read_b128 v[226:229], v6 offset:14336
	s_waitcnt lgkmcnt(3)
	v_mfma_f32_16x16x32_bf16 v[104:107], v[158:161], v[162:165], v[104:107]
	s_waitcnt lgkmcnt(2)
	v_mfma_f32_16x16x32_bf16 v[116:119], v[158:161], v[178:181], v[116:119]
	s_waitcnt lgkmcnt(1)
	s_mov_b32 m0, s40
	v_mfma_f32_16x16x32_bf16 v[128:131], v[158:161], v[222:225], v[128:131]
	global_load_lds_dwordx4 v2, s[48:49]
	s_waitcnt lgkmcnt(0)
	v_mfma_f32_16x16x32_bf16 v[100:103], v[158:161], v[226:229], v[100:103]
	ds_read_b128 v[158:161], v7 offset:33792
	v_mfma_f32_16x16x32_bf16 v[108:111], v[166:169], v[162:165], v[108:111]
	v_mfma_f32_16x16x32_bf16 v[120:123], v[166:169], v[178:181], v[120:123]
	v_mfma_f32_16x16x32_bf16 v[132:135], v[166:169], v[222:225], v[132:135]
	s_mov_b32 m0, s41
	v_mfma_f32_16x16x32_bf16 v[140:143], v[166:169], v[226:229], v[140:143]
	global_load_lds_dwordx4 v4, s[46:47]
	ds_read_b128 v[166:169], v6 offset:1024
	v_mfma_f32_16x16x32_bf16 v[112:115], v[214:217], v[162:165], v[112:115]
	v_mfma_f32_16x16x32_bf16 v[52:55], v[218:221], v[162:165], v[52:55]
	ds_read_b128 v[162:165], v7 offset:35840
	v_mfma_f32_16x16x32_bf16 v[124:127], v[214:217], v[178:181], v[124:127]
	v_mfma_f32_16x16x32_bf16 v[68:71], v[218:221], v[178:181], v[68:71]
	ds_read_b128 v[178:181], v6 offset:3072
	s_mov_b32 m0, s42
	v_mfma_f32_16x16x32_bf16 v[136:139], v[214:217], v[222:225], v[136:139]
	global_load_lds_dwordx4 v4, s[48:49]
	v_mfma_f32_16x16x32_bf16 v[84:87], v[218:221], v[222:225], v[84:87]
	ds_read_b128 v[222:225], v6 offset:5120
	v_mfma_f32_16x16x32_bf16 v[150:153], v[214:217], v[226:229], v[150:153]
	ds_read_b128 v[214:217], v7 offset:37888
	v_mfma_f32_16x16x32_bf16 v[154:157], v[218:221], v[226:229], v[154:157]
	ds_read_b128 v[218:221], v7 offset:39936
	ds_read_b128 v[226:229], v6 offset:7168
	s_waitcnt lgkmcnt(6)
	v_mfma_f32_16x16x32_bf16 v[40:43], v[158:161], v[166:169], v[40:43]
	s_waitcnt lgkmcnt(5)
	s_mov_b32 m0, s43
	v_mfma_f32_16x16x32_bf16 v[44:47], v[162:165], v[166:169], v[44:47]
	global_load_lds_dwordx4 v146, s[46:47]
	s_waitcnt lgkmcnt(4)
	v_mfma_f32_16x16x32_bf16 v[56:59], v[158:161], v[178:181], v[56:59]
	v_mfma_f32_16x16x32_bf16 v[60:63], v[162:165], v[178:181], v[60:63]
	s_waitcnt lgkmcnt(3)
	v_mfma_f32_16x16x32_bf16 v[72:75], v[158:161], v[222:225], v[72:75]
	v_mfma_f32_16x16x32_bf16 v[76:79], v[162:165], v[222:225], v[76:79]
	s_waitcnt lgkmcnt(2)
	s_mov_b32 m0, s44
	v_mfma_f32_16x16x32_bf16 v[48:51], v[214:217], v[166:169], v[48:51]
	global_load_lds_dwordx4 v146, s[48:49]
	s_waitcnt lgkmcnt(1)
	v_mfma_f32_16x16x32_bf16 v[174:177], v[218:221], v[166:169], v[174:177]
	ds_read_b128 v[166:169], v6 offset:9216
	v_mfma_f32_16x16x32_bf16 v[64:67], v[214:217], v[178:181], v[64:67]
	v_mfma_f32_16x16x32_bf16 v[170:173], v[218:221], v[178:181], v[170:173]
	ds_read_b128 v[178:181], v6 offset:11264
	v_mfma_f32_16x16x32_bf16 v[80:83], v[214:217], v[222:225], v[80:83]
	v_mfma_f32_16x16x32_bf16 v[32:35], v[218:221], v[222:225], v[32:35]
	ds_read_b128 v[222:225], v6 offset:13312
	s_waitcnt lgkmcnt(3)
	v_mfma_f32_16x16x32_bf16 v[88:91], v[158:161], v[226:229], v[88:91]
	v_mfma_f32_16x16x32_bf16 v[92:95], v[162:165], v[226:229], v[92:95]
	v_mfma_f32_16x16x32_bf16 v[96:99], v[214:217], v[226:229], v[96:99]
	v_mfma_f32_16x16x32_bf16 v[36:39], v[218:221], v[226:229], v[36:39]
	ds_read_b128 v[226:229], v6 offset:15360
	s_waitcnt lgkmcnt(3)
	v_mfma_f32_16x16x32_bf16 v[104:107], v[158:161], v[166:169], v[104:107]
	v_mfma_f32_16x16x32_bf16 v[108:111], v[162:165], v[166:169], v[108:111]
	v_mfma_f32_16x16x32_bf16 v[112:115], v[214:217], v[166:169], v[112:115]
	v_mfma_f32_16x16x32_bf16 v[52:55], v[218:221], v[166:169], v[52:55]
	s_waitcnt lgkmcnt(2)
	v_mfma_f32_16x16x32_bf16 v[116:119], v[158:161], v[178:181], v[116:119]
	v_mfma_f32_16x16x32_bf16 v[120:123], v[162:165], v[178:181], v[120:123]
	v_mfma_f32_16x16x32_bf16 v[124:127], v[214:217], v[178:181], v[124:127]
	v_mfma_f32_16x16x32_bf16 v[68:71], v[218:221], v[178:181], v[68:71]
	s_waitcnt lgkmcnt(1)
	v_mfma_f32_16x16x32_bf16 v[128:131], v[158:161], v[222:225], v[128:131]
	v_mfma_f32_16x16x32_bf16 v[132:135], v[162:165], v[222:225], v[132:135]
	v_mfma_f32_16x16x32_bf16 v[136:139], v[214:217], v[222:225], v[136:139]
	v_mfma_f32_16x16x32_bf16 v[84:87], v[218:221], v[222:225], v[84:87]
	s_waitcnt lgkmcnt(0)
	v_mfma_f32_16x16x32_bf16 v[100:103], v[158:161], v[226:229], v[100:103]
	v_mfma_f32_16x16x32_bf16 v[140:143], v[162:165], v[226:229], v[140:143]
	v_mfma_f32_16x16x32_bf16 v[150:153], v[214:217], v[226:229], v[150:153]
	v_mfma_f32_16x16x32_bf16 v[154:157], v[218:221], v[226:229], v[154:157]
	s_add_u32 s46, s0, 0x800
	s_addc_u32 s47, s1, 0
	s_add_u32 s48, s14, 0x800
	s_waitcnt vmcnt(0)
	s_barrier
	s_addc_u32 s49, s15, 0
	ds_read_b128 v[158:161], v8
	ds_read_b128 v[162:165], v12
	ds_read_b128 v[166:169], v9
	ds_read_b128 v[178:181], v13
	ds_read_b128 v[214:217], v11
	ds_read_b128 v[218:221], v10
	ds_read_b128 v[222:225], v14
	ds_read_b128 v[226:229], v15
	s_waitcnt lgkmcnt(6)
	v_mfma_f32_16x16x32_bf16 v[40:43], v[158:161], v[162:165], v[40:43]
	s_waitcnt lgkmcnt(5)
	v_mfma_f32_16x16x32_bf16 v[44:47], v[166:169], v[162:165], v[44:47]
	s_waitcnt lgkmcnt(4)
	v_mfma_f32_16x16x32_bf16 v[56:59], v[158:161], v[178:181], v[56:59]
	s_mov_b32 m0, s27
	v_mfma_f32_16x16x32_bf16 v[60:63], v[166:169], v[178:181], v[60:63]
	global_load_lds_dwordx4 v0, s[46:47]
	s_waitcnt lgkmcnt(3)
	v_mfma_f32_16x16x32_bf16 v[48:51], v[214:217], v[162:165], v[48:51]
	v_mfma_f32_16x16x32_bf16 v[64:67], v[214:217], v[178:181], v[64:67]
	s_waitcnt lgkmcnt(2)
	v_mfma_f32_16x16x32_bf16 v[174:177], v[218:221], v[162:165], v[174:177]
	ds_read_b128 v[162:165], v16
	v_mfma_f32_16x16x32_bf16 v[170:173], v[218:221], v[178:181], v[170:173]
	ds_read_b128 v[178:181], v17
	s_waitcnt lgkmcnt(3)
	s_mov_b32 m0, s28
	v_mfma_f32_16x16x32_bf16 v[72:75], v[158:161], v[222:225], v[72:75]
	global_load_lds_dwordx4 v0, s[48:49]
	v_mfma_f32_16x16x32_bf16 v[76:79], v[166:169], v[222:225], v[76:79]
	v_mfma_f32_16x16x32_bf16 v[80:83], v[214:217], v[222:225], v[80:83]
	v_mfma_f32_16x16x32_bf16 v[32:35], v[218:221], v[222:225], v[32:35]
	ds_read_b128 v[222:225], v18
	s_waitcnt lgkmcnt(3)
	v_mfma_f32_16x16x32_bf16 v[88:91], v[158:161], v[226:229], v[88:91]
	s_mov_b32 m0, s29
	v_mfma_f32_16x16x32_bf16 v[92:95], v[166:169], v[226:229], v[92:95]
	global_load_lds_dwordx4 v2, s[46:47]
	v_mfma_f32_16x16x32_bf16 v[96:99], v[214:217], v[226:229], v[96:99]
	v_mfma_f32_16x16x32_bf16 v[36:39], v[218:221], v[226:229], v[36:39]
	ds_read_b128 v[226:229], v19
	s_waitcnt lgkmcnt(3)
	v_mfma_f32_16x16x32_bf16 v[104:107], v[158:161], v[162:165], v[104:107]
	s_waitcnt lgkmcnt(2)
	v_mfma_f32_16x16x32_bf16 v[116:119], v[158:161], v[178:181], v[116:119]
	s_waitcnt lgkmcnt(1)
	s_mov_b32 m0, s30
	v_mfma_f32_16x16x32_bf16 v[128:131], v[158:161], v[222:225], v[128:131]
	global_load_lds_dwordx4 v2, s[48:49]
	s_waitcnt lgkmcnt(0)
	v_mfma_f32_16x16x32_bf16 v[100:103], v[158:161], v[226:229], v[100:103]
	ds_read_b128 v[158:161], v20
	v_mfma_f32_16x16x32_bf16 v[108:111], v[166:169], v[162:165], v[108:111]
	v_mfma_f32_16x16x32_bf16 v[120:123], v[166:169], v[178:181], v[120:123]
	v_mfma_f32_16x16x32_bf16 v[132:135], v[166:169], v[222:225], v[132:135]
	s_mov_b32 m0, s31
	v_mfma_f32_16x16x32_bf16 v[140:143], v[166:169], v[226:229], v[140:143]
	global_load_lds_dwordx4 v4, s[46:47]
	ds_read_b128 v[166:169], v24
	v_mfma_f32_16x16x32_bf16 v[112:115], v[214:217], v[162:165], v[112:115]
	v_mfma_f32_16x16x32_bf16 v[52:55], v[218:221], v[162:165], v[52:55]
	ds_read_b128 v[162:165], v21
	v_mfma_f32_16x16x32_bf16 v[124:127], v[214:217], v[178:181], v[124:127]
	v_mfma_f32_16x16x32_bf16 v[68:71], v[218:221], v[178:181], v[68:71]
	ds_read_b128 v[178:181], v25
	s_mov_b32 m0, s34
	v_mfma_f32_16x16x32_bf16 v[136:139], v[214:217], v[222:225], v[136:139]
	global_load_lds_dwordx4 v4, s[48:49]
	v_mfma_f32_16x16x32_bf16 v[84:87], v[218:221], v[222:225], v[84:87]
	ds_read_b128 v[222:225], v26
	v_mfma_f32_16x16x32_bf16 v[150:153], v[214:217], v[226:229], v[150:153]
	ds_read_b128 v[214:217], v23
	v_mfma_f32_16x16x32_bf16 v[154:157], v[218:221], v[226:229], v[154:157]
	ds_read_b128 v[218:221], v22
	ds_read_b128 v[226:229], v27
	s_waitcnt lgkmcnt(6)
	v_mfma_f32_16x16x32_bf16 v[40:43], v[158:161], v[166:169], v[40:43]
	s_waitcnt lgkmcnt(5)
	s_mov_b32 m0, s35
	v_mfma_f32_16x16x32_bf16 v[44:47], v[162:165], v[166:169], v[44:47]
	global_load_lds_dwordx4 v146, s[46:47]
	s_waitcnt lgkmcnt(4)
	v_mfma_f32_16x16x32_bf16 v[56:59], v[158:161], v[178:181], v[56:59]
	v_mfma_f32_16x16x32_bf16 v[60:63], v[162:165], v[178:181], v[60:63]
	s_waitcnt lgkmcnt(3)
	v_mfma_f32_16x16x32_bf16 v[72:75], v[158:161], v[222:225], v[72:75]
	v_mfma_f32_16x16x32_bf16 v[76:79], v[162:165], v[222:225], v[76:79]
	s_waitcnt lgkmcnt(2)
	s_mov_b32 m0, s36
	v_mfma_f32_16x16x32_bf16 v[48:51], v[214:217], v[166:169], v[48:51]
	global_load_lds_dwordx4 v146, s[48:49]
	s_waitcnt lgkmcnt(1)
	v_mfma_f32_16x16x32_bf16 v[174:177], v[218:221], v[166:169], v[174:177]
	ds_read_b128 v[166:169], v28
	v_mfma_f32_16x16x32_bf16 v[64:67], v[214:217], v[178:181], v[64:67]
	v_mfma_f32_16x16x32_bf16 v[170:173], v[218:221], v[178:181], v[170:173]
	ds_read_b128 v[178:181], v29
	v_mfma_f32_16x16x32_bf16 v[80:83], v[214:217], v[222:225], v[80:83]
	v_mfma_f32_16x16x32_bf16 v[32:35], v[218:221], v[222:225], v[32:35]
	ds_read_b128 v[222:225], v30
	s_waitcnt lgkmcnt(3)
	v_mfma_f32_16x16x32_bf16 v[88:91], v[158:161], v[226:229], v[88:91]
	v_mfma_f32_16x16x32_bf16 v[92:95], v[162:165], v[226:229], v[92:95]
	v_mfma_f32_16x16x32_bf16 v[96:99], v[214:217], v[226:229], v[96:99]
	v_mfma_f32_16x16x32_bf16 v[36:39], v[218:221], v[226:229], v[36:39]
	ds_read_b128 v[226:229], v31
	s_waitcnt lgkmcnt(3)
	v_mfma_f32_16x16x32_bf16 v[104:107], v[158:161], v[166:169], v[104:107]
	v_mfma_f32_16x16x32_bf16 v[108:111], v[162:165], v[166:169], v[108:111]
	v_mfma_f32_16x16x32_bf16 v[112:115], v[214:217], v[166:169], v[112:115]
	v_mfma_f32_16x16x32_bf16 v[52:55], v[218:221], v[166:169], v[52:55]
	s_waitcnt lgkmcnt(2)
	v_mfma_f32_16x16x32_bf16 v[116:119], v[158:161], v[178:181], v[116:119]
	v_mfma_f32_16x16x32_bf16 v[120:123], v[162:165], v[178:181], v[120:123]
	v_mfma_f32_16x16x32_bf16 v[124:127], v[214:217], v[178:181], v[124:127]
	v_mfma_f32_16x16x32_bf16 v[68:71], v[218:221], v[178:181], v[68:71]
	s_waitcnt lgkmcnt(1)
	v_mfma_f32_16x16x32_bf16 v[128:131], v[158:161], v[222:225], v[128:131]
	v_mfma_f32_16x16x32_bf16 v[132:135], v[162:165], v[222:225], v[132:135]
	v_mfma_f32_16x16x32_bf16 v[136:139], v[214:217], v[222:225], v[136:139]
	v_mfma_f32_16x16x32_bf16 v[84:87], v[218:221], v[222:225], v[84:87]
	s_waitcnt lgkmcnt(0)
	v_mfma_f32_16x16x32_bf16 v[100:103], v[158:161], v[226:229], v[100:103]
	v_mfma_f32_16x16x32_bf16 v[140:143], v[162:165], v[226:229], v[140:143]
	v_mfma_f32_16x16x32_bf16 v[150:153], v[214:217], v[226:229], v[150:153]
	v_mfma_f32_16x16x32_bf16 v[154:157], v[218:221], v[226:229], v[154:157]
	s_add_u32 s46, s0, 0x880
	s_addc_u32 s47, s1, 0
	s_add_u32 s48, s14, 0x880
	s_waitcnt vmcnt(0)
	s_barrier
	s_addc_u32 s49, s15, 0
	ds_read_b128 v[158:161], v7 offset:32768
	ds_read_b128 v[162:165], v6
	ds_read_b128 v[166:169], v7 offset:34816
	ds_read_b128 v[178:181], v6 offset:2048
	ds_read_b128 v[214:217], v7 offset:36864
	ds_read_b128 v[218:221], v7 offset:38912
	ds_read_b128 v[222:225], v6 offset:4096
	ds_read_b128 v[226:229], v6 offset:6144
	s_waitcnt lgkmcnt(6)
	v_mfma_f32_16x16x32_bf16 v[40:43], v[158:161], v[162:165], v[40:43]
	s_waitcnt lgkmcnt(5)
	v_mfma_f32_16x16x32_bf16 v[44:47], v[166:169], v[162:165], v[44:47]
	s_waitcnt lgkmcnt(4)
	v_mfma_f32_16x16x32_bf16 v[56:59], v[158:161], v[178:181], v[56:59]
	s_mov_b32 m0, s38
	v_mfma_f32_16x16x32_bf16 v[60:63], v[166:169], v[178:181], v[60:63]
	global_load_lds_dwordx4 v0, s[46:47]
	s_waitcnt lgkmcnt(3)
	v_mfma_f32_16x16x32_bf16 v[48:51], v[214:217], v[162:165], v[48:51]
	v_mfma_f32_16x16x32_bf16 v[64:67], v[214:217], v[178:181], v[64:67]
	s_waitcnt lgkmcnt(2)
	v_mfma_f32_16x16x32_bf16 v[174:177], v[218:221], v[162:165], v[174:177]
	ds_read_b128 v[162:165], v6 offset:8192
	v_mfma_f32_16x16x32_bf16 v[170:173], v[218:221], v[178:181], v[170:173]
	ds_read_b128 v[178:181], v6 offset:10240
	s_waitcnt lgkmcnt(3)
	s_mov_b32 m0, s37
	v_mfma_f32_16x16x32_bf16 v[72:75], v[158:161], v[222:225], v[72:75]
	global_load_lds_dwordx4 v0, s[48:49]
	v_mfma_f32_16x16x32_bf16 v[76:79], v[166:169], v[222:225], v[76:79]
	v_mfma_f32_16x16x32_bf16 v[80:83], v[214:217], v[222:225], v[80:83]
	v_mfma_f32_16x16x32_bf16 v[32:35], v[218:221], v[222:225], v[32:35]
	ds_read_b128 v[222:225], v6 offset:12288
	s_waitcnt lgkmcnt(3)
	v_mfma_f32_16x16x32_bf16 v[88:91], v[158:161], v[226:229], v[88:91]
	s_mov_b32 m0, s39
	v_mfma_f32_16x16x32_bf16 v[92:95], v[166:169], v[226:229], v[92:95]
	global_load_lds_dwordx4 v2, s[46:47]
	v_mfma_f32_16x16x32_bf16 v[96:99], v[214:217], v[226:229], v[96:99]
	v_mfma_f32_16x16x32_bf16 v[36:39], v[218:221], v[226:229], v[36:39]
	ds_read_b128 v[226:229], v6 offset:14336
	s_waitcnt lgkmcnt(3)
	v_mfma_f32_16x16x32_bf16 v[104:107], v[158:161], v[162:165], v[104:107]
	s_waitcnt lgkmcnt(2)
	v_mfma_f32_16x16x32_bf16 v[116:119], v[158:161], v[178:181], v[116:119]
	s_waitcnt lgkmcnt(1)
	s_mov_b32 m0, s40
	v_mfma_f32_16x16x32_bf16 v[128:131], v[158:161], v[222:225], v[128:131]
	global_load_lds_dwordx4 v2, s[48:49]
	s_waitcnt lgkmcnt(0)
	v_mfma_f32_16x16x32_bf16 v[100:103], v[158:161], v[226:229], v[100:103]
	ds_read_b128 v[158:161], v7 offset:33792
	v_mfma_f32_16x16x32_bf16 v[108:111], v[166:169], v[162:165], v[108:111]
	v_mfma_f32_16x16x32_bf16 v[120:123], v[166:169], v[178:181], v[120:123]
	v_mfma_f32_16x16x32_bf16 v[132:135], v[166:169], v[222:225], v[132:135]
	s_mov_b32 m0, s41
	v_mfma_f32_16x16x32_bf16 v[140:143], v[166:169], v[226:229], v[140:143]
	global_load_lds_dwordx4 v4, s[46:47]
	ds_read_b128 v[166:169], v6 offset:1024
	v_mfma_f32_16x16x32_bf16 v[112:115], v[214:217], v[162:165], v[112:115]
	v_mfma_f32_16x16x32_bf16 v[52:55], v[218:221], v[162:165], v[52:55]
	ds_read_b128 v[162:165], v7 offset:35840
	v_mfma_f32_16x16x32_bf16 v[124:127], v[214:217], v[178:181], v[124:127]
	v_mfma_f32_16x16x32_bf16 v[68:71], v[218:221], v[178:181], v[68:71]
	ds_read_b128 v[178:181], v6 offset:3072
	s_mov_b32 m0, s42
	v_mfma_f32_16x16x32_bf16 v[136:139], v[214:217], v[222:225], v[136:139]
	global_load_lds_dwordx4 v4, s[48:49]
	v_mfma_f32_16x16x32_bf16 v[84:87], v[218:221], v[222:225], v[84:87]
	ds_read_b128 v[222:225], v6 offset:5120
	v_mfma_f32_16x16x32_bf16 v[150:153], v[214:217], v[226:229], v[150:153]
	ds_read_b128 v[214:217], v7 offset:37888
	v_mfma_f32_16x16x32_bf16 v[154:157], v[218:221], v[226:229], v[154:157]
	ds_read_b128 v[218:221], v7 offset:39936
	ds_read_b128 v[226:229], v6 offset:7168
	s_waitcnt lgkmcnt(6)
	v_mfma_f32_16x16x32_bf16 v[40:43], v[158:161], v[166:169], v[40:43]
	s_waitcnt lgkmcnt(5)
	s_mov_b32 m0, s43
	v_mfma_f32_16x16x32_bf16 v[44:47], v[162:165], v[166:169], v[44:47]
	global_load_lds_dwordx4 v146, s[46:47]
	s_waitcnt lgkmcnt(4)
	v_mfma_f32_16x16x32_bf16 v[56:59], v[158:161], v[178:181], v[56:59]
	v_mfma_f32_16x16x32_bf16 v[60:63], v[162:165], v[178:181], v[60:63]
	s_waitcnt lgkmcnt(3)
	v_mfma_f32_16x16x32_bf16 v[72:75], v[158:161], v[222:225], v[72:75]
	v_mfma_f32_16x16x32_bf16 v[76:79], v[162:165], v[222:225], v[76:79]
	s_waitcnt lgkmcnt(2)
	s_mov_b32 m0, s44
	v_mfma_f32_16x16x32_bf16 v[48:51], v[214:217], v[166:169], v[48:51]
	global_load_lds_dwordx4 v146, s[48:49]
	s_waitcnt lgkmcnt(1)
	v_mfma_f32_16x16x32_bf16 v[174:177], v[218:221], v[166:169], v[174:177]
	ds_read_b128 v[166:169], v6 offset:9216
	v_mfma_f32_16x16x32_bf16 v[64:67], v[214:217], v[178:181], v[64:67]
	v_mfma_f32_16x16x32_bf16 v[170:173], v[218:221], v[178:181], v[170:173]
	ds_read_b128 v[178:181], v6 offset:11264
	v_mfma_f32_16x16x32_bf16 v[80:83], v[214:217], v[222:225], v[80:83]
	v_mfma_f32_16x16x32_bf16 v[32:35], v[218:221], v[222:225], v[32:35]
	ds_read_b128 v[222:225], v6 offset:13312
	s_waitcnt lgkmcnt(3)
	v_mfma_f32_16x16x32_bf16 v[88:91], v[158:161], v[226:229], v[88:91]
	v_mfma_f32_16x16x32_bf16 v[92:95], v[162:165], v[226:229], v[92:95]
	v_mfma_f32_16x16x32_bf16 v[96:99], v[214:217], v[226:229], v[96:99]
	v_mfma_f32_16x16x32_bf16 v[36:39], v[218:221], v[226:229], v[36:39]
	ds_read_b128 v[226:229], v6 offset:15360
	s_waitcnt lgkmcnt(3)
	v_mfma_f32_16x16x32_bf16 v[104:107], v[158:161], v[166:169], v[104:107]
	v_mfma_f32_16x16x32_bf16 v[108:111], v[162:165], v[166:169], v[108:111]
	v_mfma_f32_16x16x32_bf16 v[112:115], v[214:217], v[166:169], v[112:115]
	v_mfma_f32_16x16x32_bf16 v[52:55], v[218:221], v[166:169], v[52:55]
	s_waitcnt lgkmcnt(2)
	v_mfma_f32_16x16x32_bf16 v[116:119], v[158:161], v[178:181], v[116:119]
	v_mfma_f32_16x16x32_bf16 v[120:123], v[162:165], v[178:181], v[120:123]
	v_mfma_f32_16x16x32_bf16 v[124:127], v[214:217], v[178:181], v[124:127]
	v_mfma_f32_16x16x32_bf16 v[68:71], v[218:221], v[178:181], v[68:71]
	s_waitcnt lgkmcnt(1)
	v_mfma_f32_16x16x32_bf16 v[128:131], v[158:161], v[222:225], v[128:131]
	v_mfma_f32_16x16x32_bf16 v[132:135], v[162:165], v[222:225], v[132:135]
	v_mfma_f32_16x16x32_bf16 v[136:139], v[214:217], v[222:225], v[136:139]
	v_mfma_f32_16x16x32_bf16 v[84:87], v[218:221], v[222:225], v[84:87]
	s_waitcnt lgkmcnt(0)
	v_mfma_f32_16x16x32_bf16 v[100:103], v[158:161], v[226:229], v[100:103]
	v_mfma_f32_16x16x32_bf16 v[140:143], v[162:165], v[226:229], v[140:143]
	v_mfma_f32_16x16x32_bf16 v[150:153], v[214:217], v[226:229], v[150:153]
	v_mfma_f32_16x16x32_bf16 v[154:157], v[218:221], v[226:229], v[154:157]
	s_add_u32 s46, s0, 0x900
	s_addc_u32 s47, s1, 0
	s_add_u32 s48, s14, 0x900
	s_waitcnt vmcnt(0)
	s_barrier
	s_addc_u32 s49, s15, 0
	ds_read_b128 v[158:161], v8
	ds_read_b128 v[162:165], v12
	ds_read_b128 v[166:169], v9
	ds_read_b128 v[178:181], v13
	ds_read_b128 v[214:217], v11
	ds_read_b128 v[218:221], v10
	ds_read_b128 v[222:225], v14
	ds_read_b128 v[226:229], v15
	s_waitcnt lgkmcnt(6)
	v_mfma_f32_16x16x32_bf16 v[40:43], v[158:161], v[162:165], v[40:43]
	s_waitcnt lgkmcnt(5)
	v_mfma_f32_16x16x32_bf16 v[44:47], v[166:169], v[162:165], v[44:47]
	s_waitcnt lgkmcnt(4)
	v_mfma_f32_16x16x32_bf16 v[56:59], v[158:161], v[178:181], v[56:59]
	s_mov_b32 m0, s27
	v_mfma_f32_16x16x32_bf16 v[60:63], v[166:169], v[178:181], v[60:63]
	global_load_lds_dwordx4 v0, s[46:47]
	s_waitcnt lgkmcnt(3)
	v_mfma_f32_16x16x32_bf16 v[48:51], v[214:217], v[162:165], v[48:51]
	v_mfma_f32_16x16x32_bf16 v[64:67], v[214:217], v[178:181], v[64:67]
	s_waitcnt lgkmcnt(2)
	v_mfma_f32_16x16x32_bf16 v[174:177], v[218:221], v[162:165], v[174:177]
	ds_read_b128 v[162:165], v16
	v_mfma_f32_16x16x32_bf16 v[170:173], v[218:221], v[178:181], v[170:173]
	ds_read_b128 v[178:181], v17
	s_waitcnt lgkmcnt(3)
	s_mov_b32 m0, s28
	v_mfma_f32_16x16x32_bf16 v[72:75], v[158:161], v[222:225], v[72:75]
	global_load_lds_dwordx4 v0, s[48:49]
	v_mfma_f32_16x16x32_bf16 v[76:79], v[166:169], v[222:225], v[76:79]
	v_mfma_f32_16x16x32_bf16 v[80:83], v[214:217], v[222:225], v[80:83]
	v_mfma_f32_16x16x32_bf16 v[32:35], v[218:221], v[222:225], v[32:35]
	ds_read_b128 v[222:225], v18
	s_waitcnt lgkmcnt(3)
	v_mfma_f32_16x16x32_bf16 v[88:91], v[158:161], v[226:229], v[88:91]
	s_mov_b32 m0, s29
	v_mfma_f32_16x16x32_bf16 v[92:95], v[166:169], v[226:229], v[92:95]
	global_load_lds_dwordx4 v2, s[46:47]
	v_mfma_f32_16x16x32_bf16 v[96:99], v[214:217], v[226:229], v[96:99]
	v_mfma_f32_16x16x32_bf16 v[36:39], v[218:221], v[226:229], v[36:39]
	ds_read_b128 v[226:229], v19
	s_waitcnt lgkmcnt(3)
	v_mfma_f32_16x16x32_bf16 v[104:107], v[158:161], v[162:165], v[104:107]
	s_waitcnt lgkmcnt(2)
	v_mfma_f32_16x16x32_bf16 v[116:119], v[158:161], v[178:181], v[116:119]
	s_waitcnt lgkmcnt(1)
	s_mov_b32 m0, s30
	v_mfma_f32_16x16x32_bf16 v[128:131], v[158:161], v[222:225], v[128:131]
	global_load_lds_dwordx4 v2, s[48:49]
	s_waitcnt lgkmcnt(0)
	v_mfma_f32_16x16x32_bf16 v[100:103], v[158:161], v[226:229], v[100:103]
	ds_read_b128 v[158:161], v20
	v_mfma_f32_16x16x32_bf16 v[108:111], v[166:169], v[162:165], v[108:111]
	v_mfma_f32_16x16x32_bf16 v[120:123], v[166:169], v[178:181], v[120:123]
	v_mfma_f32_16x16x32_bf16 v[132:135], v[166:169], v[222:225], v[132:135]
	s_mov_b32 m0, s31
	v_mfma_f32_16x16x32_bf16 v[140:143], v[166:169], v[226:229], v[140:143]
	global_load_lds_dwordx4 v4, s[46:47]
	ds_read_b128 v[166:169], v24
	v_mfma_f32_16x16x32_bf16 v[112:115], v[214:217], v[162:165], v[112:115]
	v_mfma_f32_16x16x32_bf16 v[52:55], v[218:221], v[162:165], v[52:55]
	ds_read_b128 v[162:165], v21
	v_mfma_f32_16x16x32_bf16 v[124:127], v[214:217], v[178:181], v[124:127]
	v_mfma_f32_16x16x32_bf16 v[68:71], v[218:221], v[178:181], v[68:71]
	ds_read_b128 v[178:181], v25
	s_mov_b32 m0, s34
	v_mfma_f32_16x16x32_bf16 v[136:139], v[214:217], v[222:225], v[136:139]
	global_load_lds_dwordx4 v4, s[48:49]
	v_mfma_f32_16x16x32_bf16 v[84:87], v[218:221], v[222:225], v[84:87]
	ds_read_b128 v[222:225], v26
	v_mfma_f32_16x16x32_bf16 v[150:153], v[214:217], v[226:229], v[150:153]
	ds_read_b128 v[214:217], v23
	v_mfma_f32_16x16x32_bf16 v[154:157], v[218:221], v[226:229], v[154:157]
	ds_read_b128 v[218:221], v22
	ds_read_b128 v[226:229], v27
	s_waitcnt lgkmcnt(6)
	v_mfma_f32_16x16x32_bf16 v[40:43], v[158:161], v[166:169], v[40:43]
	s_waitcnt lgkmcnt(5)
	s_mov_b32 m0, s35
	v_mfma_f32_16x16x32_bf16 v[44:47], v[162:165], v[166:169], v[44:47]
	global_load_lds_dwordx4 v146, s[46:47]
	s_waitcnt lgkmcnt(4)
	v_mfma_f32_16x16x32_bf16 v[56:59], v[158:161], v[178:181], v[56:59]
	v_mfma_f32_16x16x32_bf16 v[60:63], v[162:165], v[178:181], v[60:63]
	s_waitcnt lgkmcnt(3)
	v_mfma_f32_16x16x32_bf16 v[72:75], v[158:161], v[222:225], v[72:75]
	v_mfma_f32_16x16x32_bf16 v[76:79], v[162:165], v[222:225], v[76:79]
	s_waitcnt lgkmcnt(2)
	s_mov_b32 m0, s36
	v_mfma_f32_16x16x32_bf16 v[48:51], v[214:217], v[166:169], v[48:51]
	global_load_lds_dwordx4 v146, s[48:49]
	s_waitcnt lgkmcnt(1)
	v_mfma_f32_16x16x32_bf16 v[174:177], v[218:221], v[166:169], v[174:177]
	ds_read_b128 v[166:169], v28
	v_mfma_f32_16x16x32_bf16 v[64:67], v[214:217], v[178:181], v[64:67]
	v_mfma_f32_16x16x32_bf16 v[170:173], v[218:221], v[178:181], v[170:173]
	ds_read_b128 v[178:181], v29
	v_mfma_f32_16x16x32_bf16 v[80:83], v[214:217], v[222:225], v[80:83]
	v_mfma_f32_16x16x32_bf16 v[32:35], v[218:221], v[222:225], v[32:35]
	ds_read_b128 v[222:225], v30
	s_waitcnt lgkmcnt(3)
	v_mfma_f32_16x16x32_bf16 v[88:91], v[158:161], v[226:229], v[88:91]
	v_mfma_f32_16x16x32_bf16 v[92:95], v[162:165], v[226:229], v[92:95]
	v_mfma_f32_16x16x32_bf16 v[96:99], v[214:217], v[226:229], v[96:99]
	v_mfma_f32_16x16x32_bf16 v[36:39], v[218:221], v[226:229], v[36:39]
	ds_read_b128 v[226:229], v31
	s_waitcnt lgkmcnt(3)
	v_mfma_f32_16x16x32_bf16 v[104:107], v[158:161], v[166:169], v[104:107]
	v_mfma_f32_16x16x32_bf16 v[108:111], v[162:165], v[166:169], v[108:111]
	v_mfma_f32_16x16x32_bf16 v[112:115], v[214:217], v[166:169], v[112:115]
	v_mfma_f32_16x16x32_bf16 v[52:55], v[218:221], v[166:169], v[52:55]
	s_waitcnt lgkmcnt(2)
	v_mfma_f32_16x16x32_bf16 v[116:119], v[158:161], v[178:181], v[116:119]
	v_mfma_f32_16x16x32_bf16 v[120:123], v[162:165], v[178:181], v[120:123]
	v_mfma_f32_16x16x32_bf16 v[124:127], v[214:217], v[178:181], v[124:127]
	v_mfma_f32_16x16x32_bf16 v[68:71], v[218:221], v[178:181], v[68:71]
	s_waitcnt lgkmcnt(1)
	v_mfma_f32_16x16x32_bf16 v[128:131], v[158:161], v[222:225], v[128:131]
	v_mfma_f32_16x16x32_bf16 v[132:135], v[162:165], v[222:225], v[132:135]
	v_mfma_f32_16x16x32_bf16 v[136:139], v[214:217], v[222:225], v[136:139]
	v_mfma_f32_16x16x32_bf16 v[84:87], v[218:221], v[222:225], v[84:87]
	s_waitcnt lgkmcnt(0)
	v_mfma_f32_16x16x32_bf16 v[100:103], v[158:161], v[226:229], v[100:103]
	v_mfma_f32_16x16x32_bf16 v[140:143], v[162:165], v[226:229], v[140:143]
	v_mfma_f32_16x16x32_bf16 v[150:153], v[214:217], v[226:229], v[150:153]
	v_mfma_f32_16x16x32_bf16 v[154:157], v[218:221], v[226:229], v[154:157]
	s_add_u32 s46, s0, 0x980
	s_addc_u32 s47, s1, 0
	s_add_u32 s48, s14, 0x980
	s_waitcnt vmcnt(0)
	s_barrier
	s_addc_u32 s49, s15, 0
	ds_read_b128 v[158:161], v7 offset:32768
	ds_read_b128 v[162:165], v6
	ds_read_b128 v[166:169], v7 offset:34816
	ds_read_b128 v[178:181], v6 offset:2048
	ds_read_b128 v[214:217], v7 offset:36864
	ds_read_b128 v[218:221], v7 offset:38912
	ds_read_b128 v[222:225], v6 offset:4096
	ds_read_b128 v[226:229], v6 offset:6144
	s_waitcnt lgkmcnt(6)
	v_mfma_f32_16x16x32_bf16 v[40:43], v[158:161], v[162:165], v[40:43]
	s_waitcnt lgkmcnt(5)
	v_mfma_f32_16x16x32_bf16 v[44:47], v[166:169], v[162:165], v[44:47]
	s_waitcnt lgkmcnt(4)
	v_mfma_f32_16x16x32_bf16 v[56:59], v[158:161], v[178:181], v[56:59]
	s_mov_b32 m0, s38
	v_mfma_f32_16x16x32_bf16 v[60:63], v[166:169], v[178:181], v[60:63]
	global_load_lds_dwordx4 v0, s[46:47]
	s_waitcnt lgkmcnt(3)
	v_mfma_f32_16x16x32_bf16 v[48:51], v[214:217], v[162:165], v[48:51]
	v_mfma_f32_16x16x32_bf16 v[64:67], v[214:217], v[178:181], v[64:67]
	s_waitcnt lgkmcnt(2)
	v_mfma_f32_16x16x32_bf16 v[174:177], v[218:221], v[162:165], v[174:177]
	ds_read_b128 v[162:165], v6 offset:8192
	v_mfma_f32_16x16x32_bf16 v[170:173], v[218:221], v[178:181], v[170:173]
	ds_read_b128 v[178:181], v6 offset:10240
	s_waitcnt lgkmcnt(3)
	s_mov_b32 m0, s37
	v_mfma_f32_16x16x32_bf16 v[72:75], v[158:161], v[222:225], v[72:75]
	global_load_lds_dwordx4 v0, s[48:49]
	v_mfma_f32_16x16x32_bf16 v[76:79], v[166:169], v[222:225], v[76:79]
	v_mfma_f32_16x16x32_bf16 v[80:83], v[214:217], v[222:225], v[80:83]
	v_mfma_f32_16x16x32_bf16 v[32:35], v[218:221], v[222:225], v[32:35]
	ds_read_b128 v[222:225], v6 offset:12288
	s_waitcnt lgkmcnt(3)
	v_mfma_f32_16x16x32_bf16 v[88:91], v[158:161], v[226:229], v[88:91]
	s_mov_b32 m0, s39
	v_mfma_f32_16x16x32_bf16 v[92:95], v[166:169], v[226:229], v[92:95]
	global_load_lds_dwordx4 v2, s[46:47]
	v_mfma_f32_16x16x32_bf16 v[96:99], v[214:217], v[226:229], v[96:99]
	v_mfma_f32_16x16x32_bf16 v[36:39], v[218:221], v[226:229], v[36:39]
	ds_read_b128 v[226:229], v6 offset:14336
	s_waitcnt lgkmcnt(3)
	v_mfma_f32_16x16x32_bf16 v[104:107], v[158:161], v[162:165], v[104:107]
	s_waitcnt lgkmcnt(2)
	v_mfma_f32_16x16x32_bf16 v[116:119], v[158:161], v[178:181], v[116:119]
	s_waitcnt lgkmcnt(1)
	s_mov_b32 m0, s40
	v_mfma_f32_16x16x32_bf16 v[128:131], v[158:161], v[222:225], v[128:131]
	global_load_lds_dwordx4 v2, s[48:49]
	s_waitcnt lgkmcnt(0)
	v_mfma_f32_16x16x32_bf16 v[100:103], v[158:161], v[226:229], v[100:103]
	ds_read_b128 v[158:161], v7 offset:33792
	v_mfma_f32_16x16x32_bf16 v[108:111], v[166:169], v[162:165], v[108:111]
	v_mfma_f32_16x16x32_bf16 v[120:123], v[166:169], v[178:181], v[120:123]
	v_mfma_f32_16x16x32_bf16 v[132:135], v[166:169], v[222:225], v[132:135]
	s_mov_b32 m0, s41
	v_mfma_f32_16x16x32_bf16 v[140:143], v[166:169], v[226:229], v[140:143]
	global_load_lds_dwordx4 v4, s[46:47]
	ds_read_b128 v[166:169], v6 offset:1024
	v_mfma_f32_16x16x32_bf16 v[112:115], v[214:217], v[162:165], v[112:115]
	v_mfma_f32_16x16x32_bf16 v[52:55], v[218:221], v[162:165], v[52:55]
	ds_read_b128 v[162:165], v7 offset:35840
	v_mfma_f32_16x16x32_bf16 v[124:127], v[214:217], v[178:181], v[124:127]
	v_mfma_f32_16x16x32_bf16 v[68:71], v[218:221], v[178:181], v[68:71]
	ds_read_b128 v[178:181], v6 offset:3072
	s_mov_b32 m0, s42
	v_mfma_f32_16x16x32_bf16 v[136:139], v[214:217], v[222:225], v[136:139]
	global_load_lds_dwordx4 v4, s[48:49]
	v_mfma_f32_16x16x32_bf16 v[84:87], v[218:221], v[222:225], v[84:87]
	ds_read_b128 v[222:225], v6 offset:5120
	v_mfma_f32_16x16x32_bf16 v[150:153], v[214:217], v[226:229], v[150:153]
	ds_read_b128 v[214:217], v7 offset:37888
	v_mfma_f32_16x16x32_bf16 v[154:157], v[218:221], v[226:229], v[154:157]
	ds_read_b128 v[218:221], v7 offset:39936
	ds_read_b128 v[226:229], v6 offset:7168
	s_waitcnt lgkmcnt(6)
	v_mfma_f32_16x16x32_bf16 v[40:43], v[158:161], v[166:169], v[40:43]
	s_waitcnt lgkmcnt(5)
	s_mov_b32 m0, s43
	v_mfma_f32_16x16x32_bf16 v[44:47], v[162:165], v[166:169], v[44:47]
	global_load_lds_dwordx4 v146, s[46:47]
	s_waitcnt lgkmcnt(4)
	v_mfma_f32_16x16x32_bf16 v[56:59], v[158:161], v[178:181], v[56:59]
	v_mfma_f32_16x16x32_bf16 v[60:63], v[162:165], v[178:181], v[60:63]
	s_waitcnt lgkmcnt(3)
	v_mfma_f32_16x16x32_bf16 v[72:75], v[158:161], v[222:225], v[72:75]
	v_mfma_f32_16x16x32_bf16 v[76:79], v[162:165], v[222:225], v[76:79]
	s_waitcnt lgkmcnt(2)
	s_mov_b32 m0, s44
	v_mfma_f32_16x16x32_bf16 v[48:51], v[214:217], v[166:169], v[48:51]
	global_load_lds_dwordx4 v146, s[48:49]
	s_waitcnt lgkmcnt(1)
	v_mfma_f32_16x16x32_bf16 v[174:177], v[218:221], v[166:169], v[174:177]
	ds_read_b128 v[166:169], v6 offset:9216
	v_mfma_f32_16x16x32_bf16 v[64:67], v[214:217], v[178:181], v[64:67]
	v_mfma_f32_16x16x32_bf16 v[170:173], v[218:221], v[178:181], v[170:173]
	ds_read_b128 v[178:181], v6 offset:11264
	v_mfma_f32_16x16x32_bf16 v[80:83], v[214:217], v[222:225], v[80:83]
	v_mfma_f32_16x16x32_bf16 v[32:35], v[218:221], v[222:225], v[32:35]
	ds_read_b128 v[222:225], v6 offset:13312
	s_waitcnt lgkmcnt(3)
	v_mfma_f32_16x16x32_bf16 v[88:91], v[158:161], v[226:229], v[88:91]
	v_mfma_f32_16x16x32_bf16 v[92:95], v[162:165], v[226:229], v[92:95]
	v_mfma_f32_16x16x32_bf16 v[96:99], v[214:217], v[226:229], v[96:99]
	v_mfma_f32_16x16x32_bf16 v[36:39], v[218:221], v[226:229], v[36:39]
	ds_read_b128 v[226:229], v6 offset:15360
	s_waitcnt lgkmcnt(3)
	v_mfma_f32_16x16x32_bf16 v[104:107], v[158:161], v[166:169], v[104:107]
	v_mfma_f32_16x16x32_bf16 v[108:111], v[162:165], v[166:169], v[108:111]
	v_mfma_f32_16x16x32_bf16 v[112:115], v[214:217], v[166:169], v[112:115]
	v_mfma_f32_16x16x32_bf16 v[52:55], v[218:221], v[166:169], v[52:55]
	s_waitcnt lgkmcnt(2)
	v_mfma_f32_16x16x32_bf16 v[116:119], v[158:161], v[178:181], v[116:119]
	v_mfma_f32_16x16x32_bf16 v[120:123], v[162:165], v[178:181], v[120:123]
	v_mfma_f32_16x16x32_bf16 v[124:127], v[214:217], v[178:181], v[124:127]
	v_mfma_f32_16x16x32_bf16 v[68:71], v[218:221], v[178:181], v[68:71]
	s_waitcnt lgkmcnt(1)
	v_mfma_f32_16x16x32_bf16 v[128:131], v[158:161], v[222:225], v[128:131]
	v_mfma_f32_16x16x32_bf16 v[132:135], v[162:165], v[222:225], v[132:135]
	v_mfma_f32_16x16x32_bf16 v[136:139], v[214:217], v[222:225], v[136:139]
	v_mfma_f32_16x16x32_bf16 v[84:87], v[218:221], v[222:225], v[84:87]
	s_waitcnt lgkmcnt(0)
	v_mfma_f32_16x16x32_bf16 v[100:103], v[158:161], v[226:229], v[100:103]
	v_mfma_f32_16x16x32_bf16 v[140:143], v[162:165], v[226:229], v[140:143]
	v_mfma_f32_16x16x32_bf16 v[150:153], v[214:217], v[226:229], v[150:153]
	v_mfma_f32_16x16x32_bf16 v[154:157], v[218:221], v[226:229], v[154:157]
	s_add_u32 s46, s0, 0xa00
	s_addc_u32 s47, s1, 0
	s_add_u32 s48, s14, 0xa00
	s_waitcnt vmcnt(0)
	s_barrier
	s_addc_u32 s49, s15, 0
	ds_read_b128 v[158:161], v8
	ds_read_b128 v[162:165], v12
	ds_read_b128 v[166:169], v9
	ds_read_b128 v[178:181], v13
	ds_read_b128 v[214:217], v11
	ds_read_b128 v[218:221], v10
	ds_read_b128 v[222:225], v14
	ds_read_b128 v[226:229], v15
	s_waitcnt lgkmcnt(6)
	v_mfma_f32_16x16x32_bf16 v[40:43], v[158:161], v[162:165], v[40:43]
	s_waitcnt lgkmcnt(5)
	v_mfma_f32_16x16x32_bf16 v[44:47], v[166:169], v[162:165], v[44:47]
	s_waitcnt lgkmcnt(4)
	v_mfma_f32_16x16x32_bf16 v[56:59], v[158:161], v[178:181], v[56:59]
	s_mov_b32 m0, s27
	v_mfma_f32_16x16x32_bf16 v[60:63], v[166:169], v[178:181], v[60:63]
	global_load_lds_dwordx4 v0, s[46:47]
	s_waitcnt lgkmcnt(3)
	v_mfma_f32_16x16x32_bf16 v[48:51], v[214:217], v[162:165], v[48:51]
	v_mfma_f32_16x16x32_bf16 v[64:67], v[214:217], v[178:181], v[64:67]
	s_waitcnt lgkmcnt(2)
	v_mfma_f32_16x16x32_bf16 v[174:177], v[218:221], v[162:165], v[174:177]
	ds_read_b128 v[162:165], v16
	v_mfma_f32_16x16x32_bf16 v[170:173], v[218:221], v[178:181], v[170:173]
	ds_read_b128 v[178:181], v17
	s_waitcnt lgkmcnt(3)
	s_mov_b32 m0, s28
	v_mfma_f32_16x16x32_bf16 v[72:75], v[158:161], v[222:225], v[72:75]
	global_load_lds_dwordx4 v0, s[48:49]
	v_mfma_f32_16x16x32_bf16 v[76:79], v[166:169], v[222:225], v[76:79]
	v_mfma_f32_16x16x32_bf16 v[80:83], v[214:217], v[222:225], v[80:83]
	v_mfma_f32_16x16x32_bf16 v[32:35], v[218:221], v[222:225], v[32:35]
	ds_read_b128 v[222:225], v18
	s_waitcnt lgkmcnt(3)
	v_mfma_f32_16x16x32_bf16 v[88:91], v[158:161], v[226:229], v[88:91]
	s_mov_b32 m0, s29
	v_mfma_f32_16x16x32_bf16 v[92:95], v[166:169], v[226:229], v[92:95]
	global_load_lds_dwordx4 v2, s[46:47]
	v_mfma_f32_16x16x32_bf16 v[96:99], v[214:217], v[226:229], v[96:99]
	v_mfma_f32_16x16x32_bf16 v[36:39], v[218:221], v[226:229], v[36:39]
	ds_read_b128 v[226:229], v19
	s_waitcnt lgkmcnt(3)
	v_mfma_f32_16x16x32_bf16 v[104:107], v[158:161], v[162:165], v[104:107]
	s_waitcnt lgkmcnt(2)
	v_mfma_f32_16x16x32_bf16 v[116:119], v[158:161], v[178:181], v[116:119]
	s_waitcnt lgkmcnt(1)
	s_mov_b32 m0, s30
	v_mfma_f32_16x16x32_bf16 v[128:131], v[158:161], v[222:225], v[128:131]
	global_load_lds_dwordx4 v2, s[48:49]
	s_waitcnt lgkmcnt(0)
	v_mfma_f32_16x16x32_bf16 v[100:103], v[158:161], v[226:229], v[100:103]
	ds_read_b128 v[158:161], v20
	v_mfma_f32_16x16x32_bf16 v[108:111], v[166:169], v[162:165], v[108:111]
	v_mfma_f32_16x16x32_bf16 v[120:123], v[166:169], v[178:181], v[120:123]
	v_mfma_f32_16x16x32_bf16 v[132:135], v[166:169], v[222:225], v[132:135]
	s_mov_b32 m0, s31
	v_mfma_f32_16x16x32_bf16 v[140:143], v[166:169], v[226:229], v[140:143]
	global_load_lds_dwordx4 v4, s[46:47]
	ds_read_b128 v[166:169], v24
	v_mfma_f32_16x16x32_bf16 v[112:115], v[214:217], v[162:165], v[112:115]
	v_mfma_f32_16x16x32_bf16 v[52:55], v[218:221], v[162:165], v[52:55]
	ds_read_b128 v[162:165], v21
	v_mfma_f32_16x16x32_bf16 v[124:127], v[214:217], v[178:181], v[124:127]
	v_mfma_f32_16x16x32_bf16 v[68:71], v[218:221], v[178:181], v[68:71]
	ds_read_b128 v[178:181], v25
	s_mov_b32 m0, s34
	v_mfma_f32_16x16x32_bf16 v[136:139], v[214:217], v[222:225], v[136:139]
	global_load_lds_dwordx4 v4, s[48:49]
	v_mfma_f32_16x16x32_bf16 v[84:87], v[218:221], v[222:225], v[84:87]
	ds_read_b128 v[222:225], v26
	v_mfma_f32_16x16x32_bf16 v[150:153], v[214:217], v[226:229], v[150:153]
	ds_read_b128 v[214:217], v23
	v_mfma_f32_16x16x32_bf16 v[154:157], v[218:221], v[226:229], v[154:157]
	ds_read_b128 v[218:221], v22
	ds_read_b128 v[226:229], v27
	s_waitcnt lgkmcnt(6)
	v_mfma_f32_16x16x32_bf16 v[40:43], v[158:161], v[166:169], v[40:43]
	s_waitcnt lgkmcnt(5)
	s_mov_b32 m0, s35
	v_mfma_f32_16x16x32_bf16 v[44:47], v[162:165], v[166:169], v[44:47]
	global_load_lds_dwordx4 v146, s[46:47]
	s_waitcnt lgkmcnt(4)
	v_mfma_f32_16x16x32_bf16 v[56:59], v[158:161], v[178:181], v[56:59]
	v_mfma_f32_16x16x32_bf16 v[60:63], v[162:165], v[178:181], v[60:63]
	s_waitcnt lgkmcnt(3)
	v_mfma_f32_16x16x32_bf16 v[72:75], v[158:161], v[222:225], v[72:75]
	v_mfma_f32_16x16x32_bf16 v[76:79], v[162:165], v[222:225], v[76:79]
	s_waitcnt lgkmcnt(2)
	s_mov_b32 m0, s36
	v_mfma_f32_16x16x32_bf16 v[48:51], v[214:217], v[166:169], v[48:51]
	global_load_lds_dwordx4 v146, s[48:49]
	s_waitcnt lgkmcnt(1)
	v_mfma_f32_16x16x32_bf16 v[174:177], v[218:221], v[166:169], v[174:177]
	ds_read_b128 v[166:169], v28
	v_mfma_f32_16x16x32_bf16 v[64:67], v[214:217], v[178:181], v[64:67]
	v_mfma_f32_16x16x32_bf16 v[170:173], v[218:221], v[178:181], v[170:173]
	ds_read_b128 v[178:181], v29
	v_mfma_f32_16x16x32_bf16 v[80:83], v[214:217], v[222:225], v[80:83]
	v_mfma_f32_16x16x32_bf16 v[32:35], v[218:221], v[222:225], v[32:35]
	ds_read_b128 v[222:225], v30
	s_waitcnt lgkmcnt(3)
	v_mfma_f32_16x16x32_bf16 v[88:91], v[158:161], v[226:229], v[88:91]
	v_mfma_f32_16x16x32_bf16 v[92:95], v[162:165], v[226:229], v[92:95]
	v_mfma_f32_16x16x32_bf16 v[96:99], v[214:217], v[226:229], v[96:99]
	v_mfma_f32_16x16x32_bf16 v[36:39], v[218:221], v[226:229], v[36:39]
	ds_read_b128 v[226:229], v31
	s_waitcnt lgkmcnt(3)
	v_mfma_f32_16x16x32_bf16 v[104:107], v[158:161], v[166:169], v[104:107]
	v_mfma_f32_16x16x32_bf16 v[108:111], v[162:165], v[166:169], v[108:111]
	v_mfma_f32_16x16x32_bf16 v[112:115], v[214:217], v[166:169], v[112:115]
	v_mfma_f32_16x16x32_bf16 v[52:55], v[218:221], v[166:169], v[52:55]
	s_waitcnt lgkmcnt(2)
	v_mfma_f32_16x16x32_bf16 v[116:119], v[158:161], v[178:181], v[116:119]
	v_mfma_f32_16x16x32_bf16 v[120:123], v[162:165], v[178:181], v[120:123]
	v_mfma_f32_16x16x32_bf16 v[124:127], v[214:217], v[178:181], v[124:127]
	v_mfma_f32_16x16x32_bf16 v[68:71], v[218:221], v[178:181], v[68:71]
	s_waitcnt lgkmcnt(1)
	v_mfma_f32_16x16x32_bf16 v[128:131], v[158:161], v[222:225], v[128:131]
	v_mfma_f32_16x16x32_bf16 v[132:135], v[162:165], v[222:225], v[132:135]
	v_mfma_f32_16x16x32_bf16 v[136:139], v[214:217], v[222:225], v[136:139]
	v_mfma_f32_16x16x32_bf16 v[84:87], v[218:221], v[222:225], v[84:87]
	s_waitcnt lgkmcnt(0)
	v_mfma_f32_16x16x32_bf16 v[100:103], v[158:161], v[226:229], v[100:103]
	v_mfma_f32_16x16x32_bf16 v[140:143], v[162:165], v[226:229], v[140:143]
	v_mfma_f32_16x16x32_bf16 v[150:153], v[214:217], v[226:229], v[150:153]
	v_mfma_f32_16x16x32_bf16 v[154:157], v[218:221], v[226:229], v[154:157]
	s_add_u32 s46, s0, 0xa80
	s_addc_u32 s47, s1, 0
	s_add_u32 s48, s14, 0xa80
	s_waitcnt vmcnt(0)
	s_barrier
	s_addc_u32 s49, s15, 0
	ds_read_b128 v[158:161], v7 offset:32768
	ds_read_b128 v[162:165], v6
	ds_read_b128 v[166:169], v7 offset:34816
	ds_read_b128 v[178:181], v6 offset:2048
	ds_read_b128 v[214:217], v7 offset:36864
	ds_read_b128 v[218:221], v7 offset:38912
	ds_read_b128 v[222:225], v6 offset:4096
	ds_read_b128 v[226:229], v6 offset:6144
	s_waitcnt lgkmcnt(6)
	v_mfma_f32_16x16x32_bf16 v[40:43], v[158:161], v[162:165], v[40:43]
	s_waitcnt lgkmcnt(5)
	v_mfma_f32_16x16x32_bf16 v[44:47], v[166:169], v[162:165], v[44:47]
	s_waitcnt lgkmcnt(4)
	v_mfma_f32_16x16x32_bf16 v[56:59], v[158:161], v[178:181], v[56:59]
	s_mov_b32 m0, s38
	v_mfma_f32_16x16x32_bf16 v[60:63], v[166:169], v[178:181], v[60:63]
	global_load_lds_dwordx4 v0, s[46:47]
	s_waitcnt lgkmcnt(3)
	v_mfma_f32_16x16x32_bf16 v[48:51], v[214:217], v[162:165], v[48:51]
	v_mfma_f32_16x16x32_bf16 v[64:67], v[214:217], v[178:181], v[64:67]
	s_waitcnt lgkmcnt(2)
	v_mfma_f32_16x16x32_bf16 v[174:177], v[218:221], v[162:165], v[174:177]
	ds_read_b128 v[162:165], v6 offset:8192
	v_mfma_f32_16x16x32_bf16 v[170:173], v[218:221], v[178:181], v[170:173]
	ds_read_b128 v[178:181], v6 offset:10240
	s_waitcnt lgkmcnt(3)
	s_mov_b32 m0, s37
	v_mfma_f32_16x16x32_bf16 v[72:75], v[158:161], v[222:225], v[72:75]
	global_load_lds_dwordx4 v0, s[48:49]
	v_mfma_f32_16x16x32_bf16 v[76:79], v[166:169], v[222:225], v[76:79]
	v_mfma_f32_16x16x32_bf16 v[80:83], v[214:217], v[222:225], v[80:83]
	v_mfma_f32_16x16x32_bf16 v[32:35], v[218:221], v[222:225], v[32:35]
	ds_read_b128 v[222:225], v6 offset:12288
	s_waitcnt lgkmcnt(3)
	v_mfma_f32_16x16x32_bf16 v[88:91], v[158:161], v[226:229], v[88:91]
	s_mov_b32 m0, s39
	v_mfma_f32_16x16x32_bf16 v[92:95], v[166:169], v[226:229], v[92:95]
	global_load_lds_dwordx4 v2, s[46:47]
	v_mfma_f32_16x16x32_bf16 v[96:99], v[214:217], v[226:229], v[96:99]
	v_mfma_f32_16x16x32_bf16 v[36:39], v[218:221], v[226:229], v[36:39]
	ds_read_b128 v[226:229], v6 offset:14336
	s_waitcnt lgkmcnt(3)
	v_mfma_f32_16x16x32_bf16 v[104:107], v[158:161], v[162:165], v[104:107]
	s_waitcnt lgkmcnt(2)
	v_mfma_f32_16x16x32_bf16 v[116:119], v[158:161], v[178:181], v[116:119]
	s_waitcnt lgkmcnt(1)
	s_mov_b32 m0, s40
	v_mfma_f32_16x16x32_bf16 v[128:131], v[158:161], v[222:225], v[128:131]
	global_load_lds_dwordx4 v2, s[48:49]
	s_waitcnt lgkmcnt(0)
	v_mfma_f32_16x16x32_bf16 v[100:103], v[158:161], v[226:229], v[100:103]
	ds_read_b128 v[158:161], v7 offset:33792
	v_mfma_f32_16x16x32_bf16 v[108:111], v[166:169], v[162:165], v[108:111]
	v_mfma_f32_16x16x32_bf16 v[120:123], v[166:169], v[178:181], v[120:123]
	v_mfma_f32_16x16x32_bf16 v[132:135], v[166:169], v[222:225], v[132:135]
	s_mov_b32 m0, s41
	v_mfma_f32_16x16x32_bf16 v[140:143], v[166:169], v[226:229], v[140:143]
	global_load_lds_dwordx4 v4, s[46:47]
	ds_read_b128 v[166:169], v6 offset:1024
	v_mfma_f32_16x16x32_bf16 v[112:115], v[214:217], v[162:165], v[112:115]
	v_mfma_f32_16x16x32_bf16 v[52:55], v[218:221], v[162:165], v[52:55]
	ds_read_b128 v[162:165], v7 offset:35840
	v_mfma_f32_16x16x32_bf16 v[124:127], v[214:217], v[178:181], v[124:127]
	v_mfma_f32_16x16x32_bf16 v[68:71], v[218:221], v[178:181], v[68:71]
	ds_read_b128 v[178:181], v6 offset:3072
	s_mov_b32 m0, s42
	v_mfma_f32_16x16x32_bf16 v[136:139], v[214:217], v[222:225], v[136:139]
	global_load_lds_dwordx4 v4, s[48:49]
	v_mfma_f32_16x16x32_bf16 v[84:87], v[218:221], v[222:225], v[84:87]
	ds_read_b128 v[222:225], v6 offset:5120
	v_mfma_f32_16x16x32_bf16 v[150:153], v[214:217], v[226:229], v[150:153]
	ds_read_b128 v[214:217], v7 offset:37888
	v_mfma_f32_16x16x32_bf16 v[154:157], v[218:221], v[226:229], v[154:157]
	ds_read_b128 v[218:221], v7 offset:39936
	ds_read_b128 v[226:229], v6 offset:7168
	s_waitcnt lgkmcnt(6)
	v_mfma_f32_16x16x32_bf16 v[40:43], v[158:161], v[166:169], v[40:43]
	s_waitcnt lgkmcnt(5)
	s_mov_b32 m0, s43
	v_mfma_f32_16x16x32_bf16 v[44:47], v[162:165], v[166:169], v[44:47]
	global_load_lds_dwordx4 v146, s[46:47]
	s_waitcnt lgkmcnt(4)
	v_mfma_f32_16x16x32_bf16 v[56:59], v[158:161], v[178:181], v[56:59]
	v_mfma_f32_16x16x32_bf16 v[60:63], v[162:165], v[178:181], v[60:63]
	s_waitcnt lgkmcnt(3)
	v_mfma_f32_16x16x32_bf16 v[72:75], v[158:161], v[222:225], v[72:75]
	v_mfma_f32_16x16x32_bf16 v[76:79], v[162:165], v[222:225], v[76:79]
	s_waitcnt lgkmcnt(2)
	s_mov_b32 m0, s44
	v_mfma_f32_16x16x32_bf16 v[48:51], v[214:217], v[166:169], v[48:51]
	global_load_lds_dwordx4 v146, s[48:49]
	s_waitcnt lgkmcnt(1)
	v_mfma_f32_16x16x32_bf16 v[174:177], v[218:221], v[166:169], v[174:177]
	ds_read_b128 v[166:169], v6 offset:9216
	v_mfma_f32_16x16x32_bf16 v[64:67], v[214:217], v[178:181], v[64:67]
	v_mfma_f32_16x16x32_bf16 v[170:173], v[218:221], v[178:181], v[170:173]
	ds_read_b128 v[178:181], v6 offset:11264
	v_mfma_f32_16x16x32_bf16 v[80:83], v[214:217], v[222:225], v[80:83]
	v_mfma_f32_16x16x32_bf16 v[32:35], v[218:221], v[222:225], v[32:35]
	ds_read_b128 v[222:225], v6 offset:13312
	s_waitcnt lgkmcnt(3)
	v_mfma_f32_16x16x32_bf16 v[88:91], v[158:161], v[226:229], v[88:91]
	v_mfma_f32_16x16x32_bf16 v[92:95], v[162:165], v[226:229], v[92:95]
	v_mfma_f32_16x16x32_bf16 v[96:99], v[214:217], v[226:229], v[96:99]
	v_mfma_f32_16x16x32_bf16 v[36:39], v[218:221], v[226:229], v[36:39]
	ds_read_b128 v[226:229], v6 offset:15360
	s_waitcnt lgkmcnt(3)
	v_mfma_f32_16x16x32_bf16 v[104:107], v[158:161], v[166:169], v[104:107]
	v_mfma_f32_16x16x32_bf16 v[108:111], v[162:165], v[166:169], v[108:111]
	v_mfma_f32_16x16x32_bf16 v[112:115], v[214:217], v[166:169], v[112:115]
	v_mfma_f32_16x16x32_bf16 v[52:55], v[218:221], v[166:169], v[52:55]
	s_waitcnt lgkmcnt(2)
	v_mfma_f32_16x16x32_bf16 v[116:119], v[158:161], v[178:181], v[116:119]
	v_mfma_f32_16x16x32_bf16 v[120:123], v[162:165], v[178:181], v[120:123]
	v_mfma_f32_16x16x32_bf16 v[124:127], v[214:217], v[178:181], v[124:127]
	v_mfma_f32_16x16x32_bf16 v[68:71], v[218:221], v[178:181], v[68:71]
	s_waitcnt lgkmcnt(1)
	v_mfma_f32_16x16x32_bf16 v[128:131], v[158:161], v[222:225], v[128:131]
	v_mfma_f32_16x16x32_bf16 v[132:135], v[162:165], v[222:225], v[132:135]
	v_mfma_f32_16x16x32_bf16 v[136:139], v[214:217], v[222:225], v[136:139]
	v_mfma_f32_16x16x32_bf16 v[84:87], v[218:221], v[222:225], v[84:87]
	s_waitcnt lgkmcnt(0)
	v_mfma_f32_16x16x32_bf16 v[100:103], v[158:161], v[226:229], v[100:103]
	v_mfma_f32_16x16x32_bf16 v[140:143], v[162:165], v[226:229], v[140:143]
	v_mfma_f32_16x16x32_bf16 v[150:153], v[214:217], v[226:229], v[150:153]
	v_mfma_f32_16x16x32_bf16 v[154:157], v[218:221], v[226:229], v[154:157]
	s_add_u32 s46, s0, 0xb00
	s_addc_u32 s47, s1, 0
	s_add_u32 s48, s14, 0xb00
	s_waitcnt vmcnt(0)
	s_barrier
	s_addc_u32 s49, s15, 0
	ds_read_b128 v[158:161], v8
	ds_read_b128 v[162:165], v12
	ds_read_b128 v[166:169], v9
	ds_read_b128 v[178:181], v13
	ds_read_b128 v[214:217], v11
	ds_read_b128 v[218:221], v10
	ds_read_b128 v[222:225], v14
	ds_read_b128 v[226:229], v15
	s_waitcnt lgkmcnt(6)
	v_mfma_f32_16x16x32_bf16 v[40:43], v[158:161], v[162:165], v[40:43]
	s_waitcnt lgkmcnt(5)
	v_mfma_f32_16x16x32_bf16 v[44:47], v[166:169], v[162:165], v[44:47]
	s_waitcnt lgkmcnt(4)
	v_mfma_f32_16x16x32_bf16 v[56:59], v[158:161], v[178:181], v[56:59]
	s_mov_b32 m0, s27
	v_mfma_f32_16x16x32_bf16 v[60:63], v[166:169], v[178:181], v[60:63]
	global_load_lds_dwordx4 v0, s[46:47]
	s_waitcnt lgkmcnt(3)
	v_mfma_f32_16x16x32_bf16 v[48:51], v[214:217], v[162:165], v[48:51]
	v_mfma_f32_16x16x32_bf16 v[64:67], v[214:217], v[178:181], v[64:67]
	s_waitcnt lgkmcnt(2)
	v_mfma_f32_16x16x32_bf16 v[174:177], v[218:221], v[162:165], v[174:177]
	ds_read_b128 v[162:165], v16
	v_mfma_f32_16x16x32_bf16 v[170:173], v[218:221], v[178:181], v[170:173]
	ds_read_b128 v[178:181], v17
	s_waitcnt lgkmcnt(3)
	s_mov_b32 m0, s28
	v_mfma_f32_16x16x32_bf16 v[72:75], v[158:161], v[222:225], v[72:75]
	global_load_lds_dwordx4 v0, s[48:49]
	v_mfma_f32_16x16x32_bf16 v[76:79], v[166:169], v[222:225], v[76:79]
	v_mfma_f32_16x16x32_bf16 v[80:83], v[214:217], v[222:225], v[80:83]
	v_mfma_f32_16x16x32_bf16 v[32:35], v[218:221], v[222:225], v[32:35]
	ds_read_b128 v[222:225], v18
	s_waitcnt lgkmcnt(3)
	v_mfma_f32_16x16x32_bf16 v[88:91], v[158:161], v[226:229], v[88:91]
	s_mov_b32 m0, s29
	v_mfma_f32_16x16x32_bf16 v[92:95], v[166:169], v[226:229], v[92:95]
	global_load_lds_dwordx4 v2, s[46:47]
	v_mfma_f32_16x16x32_bf16 v[96:99], v[214:217], v[226:229], v[96:99]
	v_mfma_f32_16x16x32_bf16 v[36:39], v[218:221], v[226:229], v[36:39]
	ds_read_b128 v[226:229], v19
	s_waitcnt lgkmcnt(3)
	v_mfma_f32_16x16x32_bf16 v[104:107], v[158:161], v[162:165], v[104:107]
	s_waitcnt lgkmcnt(2)
	v_mfma_f32_16x16x32_bf16 v[116:119], v[158:161], v[178:181], v[116:119]
	s_waitcnt lgkmcnt(1)
	s_mov_b32 m0, s30
	v_mfma_f32_16x16x32_bf16 v[128:131], v[158:161], v[222:225], v[128:131]
	global_load_lds_dwordx4 v2, s[48:49]
	s_waitcnt lgkmcnt(0)
	v_mfma_f32_16x16x32_bf16 v[100:103], v[158:161], v[226:229], v[100:103]
	ds_read_b128 v[158:161], v20
	v_mfma_f32_16x16x32_bf16 v[108:111], v[166:169], v[162:165], v[108:111]
	v_mfma_f32_16x16x32_bf16 v[120:123], v[166:169], v[178:181], v[120:123]
	v_mfma_f32_16x16x32_bf16 v[132:135], v[166:169], v[222:225], v[132:135]
	s_mov_b32 m0, s31
	v_mfma_f32_16x16x32_bf16 v[140:143], v[166:169], v[226:229], v[140:143]
	global_load_lds_dwordx4 v4, s[46:47]
	ds_read_b128 v[166:169], v24
	v_mfma_f32_16x16x32_bf16 v[112:115], v[214:217], v[162:165], v[112:115]
	v_mfma_f32_16x16x32_bf16 v[52:55], v[218:221], v[162:165], v[52:55]
	ds_read_b128 v[162:165], v21
	v_mfma_f32_16x16x32_bf16 v[124:127], v[214:217], v[178:181], v[124:127]
	v_mfma_f32_16x16x32_bf16 v[68:71], v[218:221], v[178:181], v[68:71]
	ds_read_b128 v[178:181], v25
	s_mov_b32 m0, s34
	v_mfma_f32_16x16x32_bf16 v[136:139], v[214:217], v[222:225], v[136:139]
	global_load_lds_dwordx4 v4, s[48:49]
	v_mfma_f32_16x16x32_bf16 v[84:87], v[218:221], v[222:225], v[84:87]
	ds_read_b128 v[222:225], v26
	v_mfma_f32_16x16x32_bf16 v[150:153], v[214:217], v[226:229], v[150:153]
	ds_read_b128 v[214:217], v23
	v_mfma_f32_16x16x32_bf16 v[154:157], v[218:221], v[226:229], v[154:157]
	ds_read_b128 v[218:221], v22
	ds_read_b128 v[226:229], v27
	s_waitcnt lgkmcnt(6)
	v_mfma_f32_16x16x32_bf16 v[40:43], v[158:161], v[166:169], v[40:43]
	s_waitcnt lgkmcnt(5)
	s_mov_b32 m0, s35
	v_mfma_f32_16x16x32_bf16 v[44:47], v[162:165], v[166:169], v[44:47]
	global_load_lds_dwordx4 v146, s[46:47]
	s_waitcnt lgkmcnt(4)
	v_mfma_f32_16x16x32_bf16 v[56:59], v[158:161], v[178:181], v[56:59]
	v_mfma_f32_16x16x32_bf16 v[60:63], v[162:165], v[178:181], v[60:63]
	s_waitcnt lgkmcnt(3)
	v_mfma_f32_16x16x32_bf16 v[72:75], v[158:161], v[222:225], v[72:75]
	v_mfma_f32_16x16x32_bf16 v[76:79], v[162:165], v[222:225], v[76:79]
	s_waitcnt lgkmcnt(2)
	s_mov_b32 m0, s36
	v_mfma_f32_16x16x32_bf16 v[48:51], v[214:217], v[166:169], v[48:51]
	global_load_lds_dwordx4 v146, s[48:49]
	s_waitcnt lgkmcnt(1)
	v_mfma_f32_16x16x32_bf16 v[174:177], v[218:221], v[166:169], v[174:177]
	ds_read_b128 v[166:169], v28
	v_mfma_f32_16x16x32_bf16 v[64:67], v[214:217], v[178:181], v[64:67]
	v_mfma_f32_16x16x32_bf16 v[170:173], v[218:221], v[178:181], v[170:173]
	ds_read_b128 v[178:181], v29
	v_mfma_f32_16x16x32_bf16 v[80:83], v[214:217], v[222:225], v[80:83]
	v_mfma_f32_16x16x32_bf16 v[32:35], v[218:221], v[222:225], v[32:35]
	ds_read_b128 v[222:225], v30
	s_waitcnt lgkmcnt(3)
	v_mfma_f32_16x16x32_bf16 v[88:91], v[158:161], v[226:229], v[88:91]
	v_mfma_f32_16x16x32_bf16 v[92:95], v[162:165], v[226:229], v[92:95]
	v_mfma_f32_16x16x32_bf16 v[96:99], v[214:217], v[226:229], v[96:99]
	v_mfma_f32_16x16x32_bf16 v[36:39], v[218:221], v[226:229], v[36:39]
	ds_read_b128 v[226:229], v31
	s_waitcnt lgkmcnt(3)
	v_mfma_f32_16x16x32_bf16 v[104:107], v[158:161], v[166:169], v[104:107]
	v_mfma_f32_16x16x32_bf16 v[108:111], v[162:165], v[166:169], v[108:111]
	v_mfma_f32_16x16x32_bf16 v[112:115], v[214:217], v[166:169], v[112:115]
	v_mfma_f32_16x16x32_bf16 v[52:55], v[218:221], v[166:169], v[52:55]
	s_waitcnt lgkmcnt(2)
	v_mfma_f32_16x16x32_bf16 v[116:119], v[158:161], v[178:181], v[116:119]
	v_mfma_f32_16x16x32_bf16 v[120:123], v[162:165], v[178:181], v[120:123]
	v_mfma_f32_16x16x32_bf16 v[124:127], v[214:217], v[178:181], v[124:127]
	v_mfma_f32_16x16x32_bf16 v[68:71], v[218:221], v[178:181], v[68:71]
	s_waitcnt lgkmcnt(1)
	v_mfma_f32_16x16x32_bf16 v[128:131], v[158:161], v[222:225], v[128:131]
	v_mfma_f32_16x16x32_bf16 v[132:135], v[162:165], v[222:225], v[132:135]
	v_mfma_f32_16x16x32_bf16 v[136:139], v[214:217], v[222:225], v[136:139]
	v_mfma_f32_16x16x32_bf16 v[84:87], v[218:221], v[222:225], v[84:87]
	s_waitcnt lgkmcnt(0)
	v_mfma_f32_16x16x32_bf16 v[100:103], v[158:161], v[226:229], v[100:103]
	v_mfma_f32_16x16x32_bf16 v[140:143], v[162:165], v[226:229], v[140:143]
	v_mfma_f32_16x16x32_bf16 v[150:153], v[214:217], v[226:229], v[150:153]
	v_mfma_f32_16x16x32_bf16 v[154:157], v[218:221], v[226:229], v[154:157]
	s_add_u32 s46, s0, 0xb80
	s_addc_u32 s47, s1, 0
	s_add_u32 s48, s14, 0xb80
	s_waitcnt vmcnt(0)
	s_barrier
	s_addc_u32 s49, s15, 0
	ds_read_b128 v[158:161], v7 offset:32768
	ds_read_b128 v[162:165], v6
	ds_read_b128 v[166:169], v7 offset:34816
	ds_read_b128 v[178:181], v6 offset:2048
	ds_read_b128 v[214:217], v7 offset:36864
	ds_read_b128 v[218:221], v7 offset:38912
	ds_read_b128 v[222:225], v6 offset:4096
	ds_read_b128 v[226:229], v6 offset:6144
	s_waitcnt lgkmcnt(6)
	v_mfma_f32_16x16x32_bf16 v[40:43], v[158:161], v[162:165], v[40:43]
	s_waitcnt lgkmcnt(5)
	v_mfma_f32_16x16x32_bf16 v[44:47], v[166:169], v[162:165], v[44:47]
	s_waitcnt lgkmcnt(4)
	v_mfma_f32_16x16x32_bf16 v[56:59], v[158:161], v[178:181], v[56:59]
	s_mov_b32 m0, s38
	v_mfma_f32_16x16x32_bf16 v[60:63], v[166:169], v[178:181], v[60:63]
	global_load_lds_dwordx4 v0, s[46:47]
	s_waitcnt lgkmcnt(3)
	v_mfma_f32_16x16x32_bf16 v[48:51], v[214:217], v[162:165], v[48:51]
	v_mfma_f32_16x16x32_bf16 v[64:67], v[214:217], v[178:181], v[64:67]
	s_waitcnt lgkmcnt(2)
	v_mfma_f32_16x16x32_bf16 v[174:177], v[218:221], v[162:165], v[174:177]
	ds_read_b128 v[162:165], v6 offset:8192
	v_mfma_f32_16x16x32_bf16 v[170:173], v[218:221], v[178:181], v[170:173]
	ds_read_b128 v[178:181], v6 offset:10240
	s_waitcnt lgkmcnt(3)
	s_mov_b32 m0, s37
	v_mfma_f32_16x16x32_bf16 v[72:75], v[158:161], v[222:225], v[72:75]
	global_load_lds_dwordx4 v0, s[48:49]
	v_mfma_f32_16x16x32_bf16 v[76:79], v[166:169], v[222:225], v[76:79]
	v_mfma_f32_16x16x32_bf16 v[80:83], v[214:217], v[222:225], v[80:83]
	v_mfma_f32_16x16x32_bf16 v[32:35], v[218:221], v[222:225], v[32:35]
	ds_read_b128 v[222:225], v6 offset:12288
	s_waitcnt lgkmcnt(3)
	v_mfma_f32_16x16x32_bf16 v[88:91], v[158:161], v[226:229], v[88:91]
	s_mov_b32 m0, s39
	v_mfma_f32_16x16x32_bf16 v[92:95], v[166:169], v[226:229], v[92:95]
	global_load_lds_dwordx4 v2, s[46:47]
	v_mfma_f32_16x16x32_bf16 v[96:99], v[214:217], v[226:229], v[96:99]
	v_mfma_f32_16x16x32_bf16 v[36:39], v[218:221], v[226:229], v[36:39]
	ds_read_b128 v[226:229], v6 offset:14336
	s_waitcnt lgkmcnt(3)
	v_mfma_f32_16x16x32_bf16 v[104:107], v[158:161], v[162:165], v[104:107]
	s_waitcnt lgkmcnt(2)
	v_mfma_f32_16x16x32_bf16 v[116:119], v[158:161], v[178:181], v[116:119]
	s_waitcnt lgkmcnt(1)
	s_mov_b32 m0, s40
	v_mfma_f32_16x16x32_bf16 v[128:131], v[158:161], v[222:225], v[128:131]
	global_load_lds_dwordx4 v2, s[48:49]
	s_waitcnt lgkmcnt(0)
	v_mfma_f32_16x16x32_bf16 v[100:103], v[158:161], v[226:229], v[100:103]
	ds_read_b128 v[158:161], v7 offset:33792
	v_mfma_f32_16x16x32_bf16 v[108:111], v[166:169], v[162:165], v[108:111]
	v_mfma_f32_16x16x32_bf16 v[120:123], v[166:169], v[178:181], v[120:123]
	v_mfma_f32_16x16x32_bf16 v[132:135], v[166:169], v[222:225], v[132:135]
	s_mov_b32 m0, s41
	v_mfma_f32_16x16x32_bf16 v[140:143], v[166:169], v[226:229], v[140:143]
	global_load_lds_dwordx4 v4, s[46:47]
	ds_read_b128 v[166:169], v6 offset:1024
	v_mfma_f32_16x16x32_bf16 v[112:115], v[214:217], v[162:165], v[112:115]
	v_mfma_f32_16x16x32_bf16 v[52:55], v[218:221], v[162:165], v[52:55]
	ds_read_b128 v[162:165], v7 offset:35840
	v_mfma_f32_16x16x32_bf16 v[124:127], v[214:217], v[178:181], v[124:127]
	v_mfma_f32_16x16x32_bf16 v[68:71], v[218:221], v[178:181], v[68:71]
	ds_read_b128 v[178:181], v6 offset:3072
	s_mov_b32 m0, s42
	v_mfma_f32_16x16x32_bf16 v[136:139], v[214:217], v[222:225], v[136:139]
	global_load_lds_dwordx4 v4, s[48:49]
	v_mfma_f32_16x16x32_bf16 v[84:87], v[218:221], v[222:225], v[84:87]
	ds_read_b128 v[222:225], v6 offset:5120
	v_mfma_f32_16x16x32_bf16 v[150:153], v[214:217], v[226:229], v[150:153]
	ds_read_b128 v[214:217], v7 offset:37888
	v_mfma_f32_16x16x32_bf16 v[154:157], v[218:221], v[226:229], v[154:157]
	ds_read_b128 v[218:221], v7 offset:39936
	ds_read_b128 v[226:229], v6 offset:7168
	s_waitcnt lgkmcnt(6)
	v_mfma_f32_16x16x32_bf16 v[40:43], v[158:161], v[166:169], v[40:43]
	s_waitcnt lgkmcnt(5)
	s_mov_b32 m0, s43
	v_mfma_f32_16x16x32_bf16 v[44:47], v[162:165], v[166:169], v[44:47]
	global_load_lds_dwordx4 v146, s[46:47]
	s_waitcnt lgkmcnt(4)
	v_mfma_f32_16x16x32_bf16 v[56:59], v[158:161], v[178:181], v[56:59]
	v_mfma_f32_16x16x32_bf16 v[60:63], v[162:165], v[178:181], v[60:63]
	s_waitcnt lgkmcnt(3)
	v_mfma_f32_16x16x32_bf16 v[72:75], v[158:161], v[222:225], v[72:75]
	v_mfma_f32_16x16x32_bf16 v[76:79], v[162:165], v[222:225], v[76:79]
	s_waitcnt lgkmcnt(2)
	s_mov_b32 m0, s44
	v_mfma_f32_16x16x32_bf16 v[48:51], v[214:217], v[166:169], v[48:51]
	global_load_lds_dwordx4 v146, s[48:49]
	s_waitcnt lgkmcnt(1)
	v_mfma_f32_16x16x32_bf16 v[174:177], v[218:221], v[166:169], v[174:177]
	ds_read_b128 v[166:169], v6 offset:9216
	v_mfma_f32_16x16x32_bf16 v[64:67], v[214:217], v[178:181], v[64:67]
	v_mfma_f32_16x16x32_bf16 v[170:173], v[218:221], v[178:181], v[170:173]
	ds_read_b128 v[178:181], v6 offset:11264
	v_mfma_f32_16x16x32_bf16 v[80:83], v[214:217], v[222:225], v[80:83]
	v_mfma_f32_16x16x32_bf16 v[32:35], v[218:221], v[222:225], v[32:35]
	ds_read_b128 v[222:225], v6 offset:13312
	s_waitcnt lgkmcnt(3)
	v_mfma_f32_16x16x32_bf16 v[88:91], v[158:161], v[226:229], v[88:91]
	v_mfma_f32_16x16x32_bf16 v[92:95], v[162:165], v[226:229], v[92:95]
	v_mfma_f32_16x16x32_bf16 v[96:99], v[214:217], v[226:229], v[96:99]
	v_mfma_f32_16x16x32_bf16 v[36:39], v[218:221], v[226:229], v[36:39]
	ds_read_b128 v[226:229], v6 offset:15360
	s_waitcnt lgkmcnt(3)
	v_mfma_f32_16x16x32_bf16 v[104:107], v[158:161], v[166:169], v[104:107]
	v_mfma_f32_16x16x32_bf16 v[108:111], v[162:165], v[166:169], v[108:111]
	v_mfma_f32_16x16x32_bf16 v[112:115], v[214:217], v[166:169], v[112:115]
	v_mfma_f32_16x16x32_bf16 v[52:55], v[218:221], v[166:169], v[52:55]
	s_waitcnt lgkmcnt(2)
	v_mfma_f32_16x16x32_bf16 v[116:119], v[158:161], v[178:181], v[116:119]
	v_mfma_f32_16x16x32_bf16 v[120:123], v[162:165], v[178:181], v[120:123]
	v_mfma_f32_16x16x32_bf16 v[124:127], v[214:217], v[178:181], v[124:127]
	v_mfma_f32_16x16x32_bf16 v[68:71], v[218:221], v[178:181], v[68:71]
	s_waitcnt lgkmcnt(1)
	v_mfma_f32_16x16x32_bf16 v[128:131], v[158:161], v[222:225], v[128:131]
	v_mfma_f32_16x16x32_bf16 v[132:135], v[162:165], v[222:225], v[132:135]
	v_mfma_f32_16x16x32_bf16 v[136:139], v[214:217], v[222:225], v[136:139]
	v_mfma_f32_16x16x32_bf16 v[84:87], v[218:221], v[222:225], v[84:87]
	s_waitcnt lgkmcnt(0)
	v_mfma_f32_16x16x32_bf16 v[100:103], v[158:161], v[226:229], v[100:103]
	v_mfma_f32_16x16x32_bf16 v[140:143], v[162:165], v[226:229], v[140:143]
	v_mfma_f32_16x16x32_bf16 v[150:153], v[214:217], v[226:229], v[150:153]
	v_mfma_f32_16x16x32_bf16 v[154:157], v[218:221], v[226:229], v[154:157]
	s_add_u32 s46, s0, 0xc00
	s_addc_u32 s47, s1, 0
	s_add_u32 s48, s14, 0xc00
	s_waitcnt vmcnt(0)
	s_barrier
	s_addc_u32 s49, s15, 0
	ds_read_b128 v[158:161], v8
	ds_read_b128 v[162:165], v12
	ds_read_b128 v[166:169], v9
	ds_read_b128 v[178:181], v13
	ds_read_b128 v[214:217], v11
	ds_read_b128 v[218:221], v10
	ds_read_b128 v[222:225], v14
	ds_read_b128 v[226:229], v15
	s_waitcnt lgkmcnt(6)
	v_mfma_f32_16x16x32_bf16 v[40:43], v[158:161], v[162:165], v[40:43]
	s_waitcnt lgkmcnt(5)
	v_mfma_f32_16x16x32_bf16 v[44:47], v[166:169], v[162:165], v[44:47]
	s_waitcnt lgkmcnt(4)
	v_mfma_f32_16x16x32_bf16 v[56:59], v[158:161], v[178:181], v[56:59]
	s_mov_b32 m0, s27
	v_mfma_f32_16x16x32_bf16 v[60:63], v[166:169], v[178:181], v[60:63]
	global_load_lds_dwordx4 v0, s[46:47]
	s_waitcnt lgkmcnt(3)
	v_mfma_f32_16x16x32_bf16 v[48:51], v[214:217], v[162:165], v[48:51]
	v_mfma_f32_16x16x32_bf16 v[64:67], v[214:217], v[178:181], v[64:67]
	s_waitcnt lgkmcnt(2)
	v_mfma_f32_16x16x32_bf16 v[174:177], v[218:221], v[162:165], v[174:177]
	ds_read_b128 v[162:165], v16
	v_mfma_f32_16x16x32_bf16 v[170:173], v[218:221], v[178:181], v[170:173]
	ds_read_b128 v[178:181], v17
	s_waitcnt lgkmcnt(3)
	s_mov_b32 m0, s28
	v_mfma_f32_16x16x32_bf16 v[72:75], v[158:161], v[222:225], v[72:75]
	global_load_lds_dwordx4 v0, s[48:49]
	v_mfma_f32_16x16x32_bf16 v[76:79], v[166:169], v[222:225], v[76:79]
	v_mfma_f32_16x16x32_bf16 v[80:83], v[214:217], v[222:225], v[80:83]
	v_mfma_f32_16x16x32_bf16 v[32:35], v[218:221], v[222:225], v[32:35]
	ds_read_b128 v[222:225], v18
	s_waitcnt lgkmcnt(3)
	v_mfma_f32_16x16x32_bf16 v[88:91], v[158:161], v[226:229], v[88:91]
	s_mov_b32 m0, s29
	v_mfma_f32_16x16x32_bf16 v[92:95], v[166:169], v[226:229], v[92:95]
	global_load_lds_dwordx4 v2, s[46:47]
	v_mfma_f32_16x16x32_bf16 v[96:99], v[214:217], v[226:229], v[96:99]
	v_mfma_f32_16x16x32_bf16 v[36:39], v[218:221], v[226:229], v[36:39]
	ds_read_b128 v[226:229], v19
	s_waitcnt lgkmcnt(3)
	v_mfma_f32_16x16x32_bf16 v[104:107], v[158:161], v[162:165], v[104:107]
	s_waitcnt lgkmcnt(2)
	v_mfma_f32_16x16x32_bf16 v[116:119], v[158:161], v[178:181], v[116:119]
	s_waitcnt lgkmcnt(1)
	s_mov_b32 m0, s30
	v_mfma_f32_16x16x32_bf16 v[128:131], v[158:161], v[222:225], v[128:131]
	global_load_lds_dwordx4 v2, s[48:49]
	s_waitcnt lgkmcnt(0)
	v_mfma_f32_16x16x32_bf16 v[100:103], v[158:161], v[226:229], v[100:103]
	ds_read_b128 v[158:161], v20
	v_mfma_f32_16x16x32_bf16 v[108:111], v[166:169], v[162:165], v[108:111]
	v_mfma_f32_16x16x32_bf16 v[120:123], v[166:169], v[178:181], v[120:123]
	v_mfma_f32_16x16x32_bf16 v[132:135], v[166:169], v[222:225], v[132:135]
	s_mov_b32 m0, s31
	v_mfma_f32_16x16x32_bf16 v[140:143], v[166:169], v[226:229], v[140:143]
	global_load_lds_dwordx4 v4, s[46:47]
	ds_read_b128 v[166:169], v24
	v_mfma_f32_16x16x32_bf16 v[112:115], v[214:217], v[162:165], v[112:115]
	v_mfma_f32_16x16x32_bf16 v[52:55], v[218:221], v[162:165], v[52:55]
	ds_read_b128 v[162:165], v21
	v_mfma_f32_16x16x32_bf16 v[124:127], v[214:217], v[178:181], v[124:127]
	v_mfma_f32_16x16x32_bf16 v[68:71], v[218:221], v[178:181], v[68:71]
	ds_read_b128 v[178:181], v25
	s_mov_b32 m0, s34
	v_mfma_f32_16x16x32_bf16 v[136:139], v[214:217], v[222:225], v[136:139]
	global_load_lds_dwordx4 v4, s[48:49]
	v_mfma_f32_16x16x32_bf16 v[84:87], v[218:221], v[222:225], v[84:87]
	ds_read_b128 v[222:225], v26
	v_mfma_f32_16x16x32_bf16 v[150:153], v[214:217], v[226:229], v[150:153]
	ds_read_b128 v[214:217], v23
	v_mfma_f32_16x16x32_bf16 v[154:157], v[218:221], v[226:229], v[154:157]
	ds_read_b128 v[218:221], v22
	ds_read_b128 v[226:229], v27
	s_waitcnt lgkmcnt(6)
	v_mfma_f32_16x16x32_bf16 v[40:43], v[158:161], v[166:169], v[40:43]
	s_waitcnt lgkmcnt(5)
	s_mov_b32 m0, s35
	v_mfma_f32_16x16x32_bf16 v[44:47], v[162:165], v[166:169], v[44:47]
	global_load_lds_dwordx4 v146, s[46:47]
	s_waitcnt lgkmcnt(4)
	v_mfma_f32_16x16x32_bf16 v[56:59], v[158:161], v[178:181], v[56:59]
	v_mfma_f32_16x16x32_bf16 v[60:63], v[162:165], v[178:181], v[60:63]
	s_waitcnt lgkmcnt(3)
	v_mfma_f32_16x16x32_bf16 v[72:75], v[158:161], v[222:225], v[72:75]
	v_mfma_f32_16x16x32_bf16 v[76:79], v[162:165], v[222:225], v[76:79]
	s_waitcnt lgkmcnt(2)
	s_mov_b32 m0, s36
	v_mfma_f32_16x16x32_bf16 v[48:51], v[214:217], v[166:169], v[48:51]
	global_load_lds_dwordx4 v146, s[48:49]
	s_waitcnt lgkmcnt(1)
	v_mfma_f32_16x16x32_bf16 v[174:177], v[218:221], v[166:169], v[174:177]
	ds_read_b128 v[166:169], v28
	v_mfma_f32_16x16x32_bf16 v[64:67], v[214:217], v[178:181], v[64:67]
	v_mfma_f32_16x16x32_bf16 v[170:173], v[218:221], v[178:181], v[170:173]
	ds_read_b128 v[178:181], v29
	v_mfma_f32_16x16x32_bf16 v[80:83], v[214:217], v[222:225], v[80:83]
	v_mfma_f32_16x16x32_bf16 v[32:35], v[218:221], v[222:225], v[32:35]
	ds_read_b128 v[222:225], v30
	s_waitcnt lgkmcnt(3)
	v_mfma_f32_16x16x32_bf16 v[88:91], v[158:161], v[226:229], v[88:91]
	v_mfma_f32_16x16x32_bf16 v[92:95], v[162:165], v[226:229], v[92:95]
	v_mfma_f32_16x16x32_bf16 v[96:99], v[214:217], v[226:229], v[96:99]
	v_mfma_f32_16x16x32_bf16 v[36:39], v[218:221], v[226:229], v[36:39]
	ds_read_b128 v[226:229], v31
	s_waitcnt lgkmcnt(3)
	v_mfma_f32_16x16x32_bf16 v[104:107], v[158:161], v[166:169], v[104:107]
	v_mfma_f32_16x16x32_bf16 v[108:111], v[162:165], v[166:169], v[108:111]
	v_mfma_f32_16x16x32_bf16 v[112:115], v[214:217], v[166:169], v[112:115]
	v_mfma_f32_16x16x32_bf16 v[52:55], v[218:221], v[166:169], v[52:55]
	s_waitcnt lgkmcnt(2)
	v_mfma_f32_16x16x32_bf16 v[116:119], v[158:161], v[178:181], v[116:119]
	v_mfma_f32_16x16x32_bf16 v[120:123], v[162:165], v[178:181], v[120:123]
	v_mfma_f32_16x16x32_bf16 v[124:127], v[214:217], v[178:181], v[124:127]
	v_mfma_f32_16x16x32_bf16 v[68:71], v[218:221], v[178:181], v[68:71]
	s_waitcnt lgkmcnt(1)
	v_mfma_f32_16x16x32_bf16 v[128:131], v[158:161], v[222:225], v[128:131]
	v_mfma_f32_16x16x32_bf16 v[132:135], v[162:165], v[222:225], v[132:135]
	v_mfma_f32_16x16x32_bf16 v[136:139], v[214:217], v[222:225], v[136:139]
	v_mfma_f32_16x16x32_bf16 v[84:87], v[218:221], v[222:225], v[84:87]
	s_waitcnt lgkmcnt(0)
	v_mfma_f32_16x16x32_bf16 v[100:103], v[158:161], v[226:229], v[100:103]
	v_mfma_f32_16x16x32_bf16 v[140:143], v[162:165], v[226:229], v[140:143]
	v_mfma_f32_16x16x32_bf16 v[150:153], v[214:217], v[226:229], v[150:153]
	v_mfma_f32_16x16x32_bf16 v[154:157], v[218:221], v[226:229], v[154:157]
	s_add_u32 s46, s0, 0xc80
	s_addc_u32 s47, s1, 0
	s_add_u32 s48, s14, 0xc80
	s_waitcnt vmcnt(0)
	s_barrier
	s_addc_u32 s49, s15, 0
	ds_read_b128 v[158:161], v7 offset:32768
	ds_read_b128 v[162:165], v6
	ds_read_b128 v[166:169], v7 offset:34816
	ds_read_b128 v[178:181], v6 offset:2048
	ds_read_b128 v[214:217], v7 offset:36864
	ds_read_b128 v[218:221], v7 offset:38912
	ds_read_b128 v[222:225], v6 offset:4096
	ds_read_b128 v[226:229], v6 offset:6144
	s_waitcnt lgkmcnt(6)
	v_mfma_f32_16x16x32_bf16 v[40:43], v[158:161], v[162:165], v[40:43]
	s_waitcnt lgkmcnt(5)
	v_mfma_f32_16x16x32_bf16 v[44:47], v[166:169], v[162:165], v[44:47]
	s_waitcnt lgkmcnt(4)
	v_mfma_f32_16x16x32_bf16 v[56:59], v[158:161], v[178:181], v[56:59]
	s_mov_b32 m0, s38
	v_mfma_f32_16x16x32_bf16 v[60:63], v[166:169], v[178:181], v[60:63]
	global_load_lds_dwordx4 v0, s[46:47]
	s_waitcnt lgkmcnt(3)
	v_mfma_f32_16x16x32_bf16 v[48:51], v[214:217], v[162:165], v[48:51]
	v_mfma_f32_16x16x32_bf16 v[64:67], v[214:217], v[178:181], v[64:67]
	s_waitcnt lgkmcnt(2)
	v_mfma_f32_16x16x32_bf16 v[174:177], v[218:221], v[162:165], v[174:177]
	ds_read_b128 v[162:165], v6 offset:8192
	v_mfma_f32_16x16x32_bf16 v[170:173], v[218:221], v[178:181], v[170:173]
	ds_read_b128 v[178:181], v6 offset:10240
	s_waitcnt lgkmcnt(3)
	s_mov_b32 m0, s37
	v_mfma_f32_16x16x32_bf16 v[72:75], v[158:161], v[222:225], v[72:75]
	global_load_lds_dwordx4 v0, s[48:49]
	v_mfma_f32_16x16x32_bf16 v[76:79], v[166:169], v[222:225], v[76:79]
	v_mfma_f32_16x16x32_bf16 v[80:83], v[214:217], v[222:225], v[80:83]
	v_mfma_f32_16x16x32_bf16 v[32:35], v[218:221], v[222:225], v[32:35]
	ds_read_b128 v[222:225], v6 offset:12288
	s_waitcnt lgkmcnt(3)
	v_mfma_f32_16x16x32_bf16 v[88:91], v[158:161], v[226:229], v[88:91]
	s_mov_b32 m0, s39
	v_mfma_f32_16x16x32_bf16 v[92:95], v[166:169], v[226:229], v[92:95]
	global_load_lds_dwordx4 v2, s[46:47]
	v_mfma_f32_16x16x32_bf16 v[96:99], v[214:217], v[226:229], v[96:99]
	v_mfma_f32_16x16x32_bf16 v[36:39], v[218:221], v[226:229], v[36:39]
	ds_read_b128 v[226:229], v6 offset:14336
	s_waitcnt lgkmcnt(3)
	v_mfma_f32_16x16x32_bf16 v[104:107], v[158:161], v[162:165], v[104:107]
	s_waitcnt lgkmcnt(2)
	v_mfma_f32_16x16x32_bf16 v[116:119], v[158:161], v[178:181], v[116:119]
	s_waitcnt lgkmcnt(1)
	s_mov_b32 m0, s40
	v_mfma_f32_16x16x32_bf16 v[128:131], v[158:161], v[222:225], v[128:131]
	global_load_lds_dwordx4 v2, s[48:49]
	s_waitcnt lgkmcnt(0)
	v_mfma_f32_16x16x32_bf16 v[100:103], v[158:161], v[226:229], v[100:103]
	ds_read_b128 v[158:161], v7 offset:33792
	v_mfma_f32_16x16x32_bf16 v[108:111], v[166:169], v[162:165], v[108:111]
	v_mfma_f32_16x16x32_bf16 v[120:123], v[166:169], v[178:181], v[120:123]
	v_mfma_f32_16x16x32_bf16 v[132:135], v[166:169], v[222:225], v[132:135]
	s_mov_b32 m0, s41
	v_mfma_f32_16x16x32_bf16 v[140:143], v[166:169], v[226:229], v[140:143]
	global_load_lds_dwordx4 v4, s[46:47]
	ds_read_b128 v[166:169], v6 offset:1024
	v_mfma_f32_16x16x32_bf16 v[112:115], v[214:217], v[162:165], v[112:115]
	v_mfma_f32_16x16x32_bf16 v[52:55], v[218:221], v[162:165], v[52:55]
	ds_read_b128 v[162:165], v7 offset:35840
	v_mfma_f32_16x16x32_bf16 v[124:127], v[214:217], v[178:181], v[124:127]
	v_mfma_f32_16x16x32_bf16 v[68:71], v[218:221], v[178:181], v[68:71]
	ds_read_b128 v[178:181], v6 offset:3072
	s_mov_b32 m0, s42
	v_mfma_f32_16x16x32_bf16 v[136:139], v[214:217], v[222:225], v[136:139]
	global_load_lds_dwordx4 v4, s[48:49]
	v_mfma_f32_16x16x32_bf16 v[84:87], v[218:221], v[222:225], v[84:87]
	ds_read_b128 v[222:225], v6 offset:5120
	v_mfma_f32_16x16x32_bf16 v[150:153], v[214:217], v[226:229], v[150:153]
	ds_read_b128 v[214:217], v7 offset:37888
	v_mfma_f32_16x16x32_bf16 v[154:157], v[218:221], v[226:229], v[154:157]
	ds_read_b128 v[218:221], v7 offset:39936
	ds_read_b128 v[226:229], v6 offset:7168
	s_waitcnt lgkmcnt(6)
	v_mfma_f32_16x16x32_bf16 v[40:43], v[158:161], v[166:169], v[40:43]
	s_waitcnt lgkmcnt(5)
	s_mov_b32 m0, s43
	v_mfma_f32_16x16x32_bf16 v[44:47], v[162:165], v[166:169], v[44:47]
	global_load_lds_dwordx4 v146, s[46:47]
	s_waitcnt lgkmcnt(4)
	v_mfma_f32_16x16x32_bf16 v[56:59], v[158:161], v[178:181], v[56:59]
	v_mfma_f32_16x16x32_bf16 v[60:63], v[162:165], v[178:181], v[60:63]
	s_waitcnt lgkmcnt(3)
	v_mfma_f32_16x16x32_bf16 v[72:75], v[158:161], v[222:225], v[72:75]
	v_mfma_f32_16x16x32_bf16 v[76:79], v[162:165], v[222:225], v[76:79]
	s_waitcnt lgkmcnt(2)
	s_mov_b32 m0, s44
	v_mfma_f32_16x16x32_bf16 v[48:51], v[214:217], v[166:169], v[48:51]
	global_load_lds_dwordx4 v146, s[48:49]
	s_waitcnt lgkmcnt(1)
	v_mfma_f32_16x16x32_bf16 v[174:177], v[218:221], v[166:169], v[174:177]
	ds_read_b128 v[166:169], v6 offset:9216
	v_mfma_f32_16x16x32_bf16 v[64:67], v[214:217], v[178:181], v[64:67]
	v_mfma_f32_16x16x32_bf16 v[170:173], v[218:221], v[178:181], v[170:173]
	ds_read_b128 v[178:181], v6 offset:11264
	v_mfma_f32_16x16x32_bf16 v[80:83], v[214:217], v[222:225], v[80:83]
	v_mfma_f32_16x16x32_bf16 v[32:35], v[218:221], v[222:225], v[32:35]
	ds_read_b128 v[222:225], v6 offset:13312
	s_waitcnt lgkmcnt(3)
	v_mfma_f32_16x16x32_bf16 v[88:91], v[158:161], v[226:229], v[88:91]
	v_mfma_f32_16x16x32_bf16 v[92:95], v[162:165], v[226:229], v[92:95]
	v_mfma_f32_16x16x32_bf16 v[96:99], v[214:217], v[226:229], v[96:99]
	v_mfma_f32_16x16x32_bf16 v[36:39], v[218:221], v[226:229], v[36:39]
	ds_read_b128 v[226:229], v6 offset:15360
	s_waitcnt lgkmcnt(3)
	v_mfma_f32_16x16x32_bf16 v[104:107], v[158:161], v[166:169], v[104:107]
	v_mfma_f32_16x16x32_bf16 v[108:111], v[162:165], v[166:169], v[108:111]
	v_mfma_f32_16x16x32_bf16 v[112:115], v[214:217], v[166:169], v[112:115]
	v_mfma_f32_16x16x32_bf16 v[52:55], v[218:221], v[166:169], v[52:55]
	s_waitcnt lgkmcnt(2)
	v_mfma_f32_16x16x32_bf16 v[116:119], v[158:161], v[178:181], v[116:119]
	v_mfma_f32_16x16x32_bf16 v[120:123], v[162:165], v[178:181], v[120:123]
	v_mfma_f32_16x16x32_bf16 v[124:127], v[214:217], v[178:181], v[124:127]
	v_mfma_f32_16x16x32_bf16 v[68:71], v[218:221], v[178:181], v[68:71]
	s_waitcnt lgkmcnt(1)
	v_mfma_f32_16x16x32_bf16 v[128:131], v[158:161], v[222:225], v[128:131]
	v_mfma_f32_16x16x32_bf16 v[132:135], v[162:165], v[222:225], v[132:135]
	v_mfma_f32_16x16x32_bf16 v[136:139], v[214:217], v[222:225], v[136:139]
	v_mfma_f32_16x16x32_bf16 v[84:87], v[218:221], v[222:225], v[84:87]
	s_waitcnt lgkmcnt(0)
	v_mfma_f32_16x16x32_bf16 v[100:103], v[158:161], v[226:229], v[100:103]
	v_mfma_f32_16x16x32_bf16 v[140:143], v[162:165], v[226:229], v[140:143]
	v_mfma_f32_16x16x32_bf16 v[150:153], v[214:217], v[226:229], v[150:153]
	v_mfma_f32_16x16x32_bf16 v[154:157], v[218:221], v[226:229], v[154:157]
	s_add_u32 s46, s0, 0xd00
	s_addc_u32 s47, s1, 0
	s_add_u32 s48, s14, 0xd00
	s_waitcnt vmcnt(0)
	s_barrier
	s_addc_u32 s49, s15, 0
	ds_read_b128 v[158:161], v8
	ds_read_b128 v[162:165], v12
	ds_read_b128 v[166:169], v9
	ds_read_b128 v[178:181], v13
	ds_read_b128 v[214:217], v11
	ds_read_b128 v[218:221], v10
	ds_read_b128 v[222:225], v14
	ds_read_b128 v[226:229], v15
	s_waitcnt lgkmcnt(6)
	v_mfma_f32_16x16x32_bf16 v[40:43], v[158:161], v[162:165], v[40:43]
	s_waitcnt lgkmcnt(5)
	v_mfma_f32_16x16x32_bf16 v[44:47], v[166:169], v[162:165], v[44:47]
	s_waitcnt lgkmcnt(4)
	v_mfma_f32_16x16x32_bf16 v[56:59], v[158:161], v[178:181], v[56:59]
	s_mov_b32 m0, s27
	v_mfma_f32_16x16x32_bf16 v[60:63], v[166:169], v[178:181], v[60:63]
	global_load_lds_dwordx4 v0, s[46:47]
	s_waitcnt lgkmcnt(3)
	v_mfma_f32_16x16x32_bf16 v[48:51], v[214:217], v[162:165], v[48:51]
	v_mfma_f32_16x16x32_bf16 v[64:67], v[214:217], v[178:181], v[64:67]
	s_waitcnt lgkmcnt(2)
	v_mfma_f32_16x16x32_bf16 v[174:177], v[218:221], v[162:165], v[174:177]
	ds_read_b128 v[162:165], v16
	v_mfma_f32_16x16x32_bf16 v[170:173], v[218:221], v[178:181], v[170:173]
	ds_read_b128 v[178:181], v17
	s_waitcnt lgkmcnt(3)
	s_mov_b32 m0, s28
	v_mfma_f32_16x16x32_bf16 v[72:75], v[158:161], v[222:225], v[72:75]
	global_load_lds_dwordx4 v0, s[48:49]
	v_mfma_f32_16x16x32_bf16 v[76:79], v[166:169], v[222:225], v[76:79]
	v_mfma_f32_16x16x32_bf16 v[80:83], v[214:217], v[222:225], v[80:83]
	v_mfma_f32_16x16x32_bf16 v[32:35], v[218:221], v[222:225], v[32:35]
	ds_read_b128 v[222:225], v18
	s_waitcnt lgkmcnt(3)
	v_mfma_f32_16x16x32_bf16 v[88:91], v[158:161], v[226:229], v[88:91]
	s_mov_b32 m0, s29
	v_mfma_f32_16x16x32_bf16 v[92:95], v[166:169], v[226:229], v[92:95]
	global_load_lds_dwordx4 v2, s[46:47]
	v_mfma_f32_16x16x32_bf16 v[96:99], v[214:217], v[226:229], v[96:99]
	v_mfma_f32_16x16x32_bf16 v[36:39], v[218:221], v[226:229], v[36:39]
	ds_read_b128 v[226:229], v19
	s_waitcnt lgkmcnt(3)
	v_mfma_f32_16x16x32_bf16 v[104:107], v[158:161], v[162:165], v[104:107]
	s_waitcnt lgkmcnt(2)
	v_mfma_f32_16x16x32_bf16 v[116:119], v[158:161], v[178:181], v[116:119]
	s_waitcnt lgkmcnt(1)
	s_mov_b32 m0, s30
	v_mfma_f32_16x16x32_bf16 v[128:131], v[158:161], v[222:225], v[128:131]
	global_load_lds_dwordx4 v2, s[48:49]
	s_waitcnt lgkmcnt(0)
	v_mfma_f32_16x16x32_bf16 v[100:103], v[158:161], v[226:229], v[100:103]
	ds_read_b128 v[158:161], v20
	v_mfma_f32_16x16x32_bf16 v[108:111], v[166:169], v[162:165], v[108:111]
	v_mfma_f32_16x16x32_bf16 v[120:123], v[166:169], v[178:181], v[120:123]
	v_mfma_f32_16x16x32_bf16 v[132:135], v[166:169], v[222:225], v[132:135]
	s_mov_b32 m0, s31
	v_mfma_f32_16x16x32_bf16 v[140:143], v[166:169], v[226:229], v[140:143]
	global_load_lds_dwordx4 v4, s[46:47]
	ds_read_b128 v[166:169], v24
	v_mfma_f32_16x16x32_bf16 v[112:115], v[214:217], v[162:165], v[112:115]
	v_mfma_f32_16x16x32_bf16 v[52:55], v[218:221], v[162:165], v[52:55]
	ds_read_b128 v[162:165], v21
	v_mfma_f32_16x16x32_bf16 v[124:127], v[214:217], v[178:181], v[124:127]
	v_mfma_f32_16x16x32_bf16 v[68:71], v[218:221], v[178:181], v[68:71]
	ds_read_b128 v[178:181], v25
	s_mov_b32 m0, s34
	v_mfma_f32_16x16x32_bf16 v[136:139], v[214:217], v[222:225], v[136:139]
	global_load_lds_dwordx4 v4, s[48:49]
	v_mfma_f32_16x16x32_bf16 v[84:87], v[218:221], v[222:225], v[84:87]
	ds_read_b128 v[222:225], v26
	v_mfma_f32_16x16x32_bf16 v[150:153], v[214:217], v[226:229], v[150:153]
	ds_read_b128 v[214:217], v23
	v_mfma_f32_16x16x32_bf16 v[154:157], v[218:221], v[226:229], v[154:157]
	ds_read_b128 v[218:221], v22
	ds_read_b128 v[226:229], v27
	s_waitcnt lgkmcnt(6)
	v_mfma_f32_16x16x32_bf16 v[40:43], v[158:161], v[166:169], v[40:43]
	s_waitcnt lgkmcnt(5)
	s_mov_b32 m0, s35
	v_mfma_f32_16x16x32_bf16 v[44:47], v[162:165], v[166:169], v[44:47]
	global_load_lds_dwordx4 v146, s[46:47]
	s_waitcnt lgkmcnt(4)
	v_mfma_f32_16x16x32_bf16 v[56:59], v[158:161], v[178:181], v[56:59]
	v_mfma_f32_16x16x32_bf16 v[60:63], v[162:165], v[178:181], v[60:63]
	s_waitcnt lgkmcnt(3)
	v_mfma_f32_16x16x32_bf16 v[72:75], v[158:161], v[222:225], v[72:75]
	v_mfma_f32_16x16x32_bf16 v[76:79], v[162:165], v[222:225], v[76:79]
	s_waitcnt lgkmcnt(2)
	s_mov_b32 m0, s36
	v_mfma_f32_16x16x32_bf16 v[48:51], v[214:217], v[166:169], v[48:51]
	global_load_lds_dwordx4 v146, s[48:49]
	s_waitcnt lgkmcnt(1)
	v_mfma_f32_16x16x32_bf16 v[174:177], v[218:221], v[166:169], v[174:177]
	ds_read_b128 v[166:169], v28
	v_mfma_f32_16x16x32_bf16 v[64:67], v[214:217], v[178:181], v[64:67]
	v_mfma_f32_16x16x32_bf16 v[170:173], v[218:221], v[178:181], v[170:173]
	ds_read_b128 v[178:181], v29
	v_mfma_f32_16x16x32_bf16 v[80:83], v[214:217], v[222:225], v[80:83]
	v_mfma_f32_16x16x32_bf16 v[32:35], v[218:221], v[222:225], v[32:35]
	ds_read_b128 v[222:225], v30
	s_waitcnt lgkmcnt(3)
	v_mfma_f32_16x16x32_bf16 v[88:91], v[158:161], v[226:229], v[88:91]
	v_mfma_f32_16x16x32_bf16 v[92:95], v[162:165], v[226:229], v[92:95]
	v_mfma_f32_16x16x32_bf16 v[96:99], v[214:217], v[226:229], v[96:99]
	v_mfma_f32_16x16x32_bf16 v[36:39], v[218:221], v[226:229], v[36:39]
	ds_read_b128 v[226:229], v31
	s_waitcnt lgkmcnt(3)
	v_mfma_f32_16x16x32_bf16 v[104:107], v[158:161], v[166:169], v[104:107]
	v_mfma_f32_16x16x32_bf16 v[108:111], v[162:165], v[166:169], v[108:111]
	v_mfma_f32_16x16x32_bf16 v[112:115], v[214:217], v[166:169], v[112:115]
	v_mfma_f32_16x16x32_bf16 v[52:55], v[218:221], v[166:169], v[52:55]
	s_waitcnt lgkmcnt(2)
	v_mfma_f32_16x16x32_bf16 v[116:119], v[158:161], v[178:181], v[116:119]
	v_mfma_f32_16x16x32_bf16 v[120:123], v[162:165], v[178:181], v[120:123]
	v_mfma_f32_16x16x32_bf16 v[124:127], v[214:217], v[178:181], v[124:127]
	v_mfma_f32_16x16x32_bf16 v[68:71], v[218:221], v[178:181], v[68:71]
	s_waitcnt lgkmcnt(1)
	v_mfma_f32_16x16x32_bf16 v[128:131], v[158:161], v[222:225], v[128:131]
	v_mfma_f32_16x16x32_bf16 v[132:135], v[162:165], v[222:225], v[132:135]
	v_mfma_f32_16x16x32_bf16 v[136:139], v[214:217], v[222:225], v[136:139]
	v_mfma_f32_16x16x32_bf16 v[84:87], v[218:221], v[222:225], v[84:87]
	s_waitcnt lgkmcnt(0)
	v_mfma_f32_16x16x32_bf16 v[100:103], v[158:161], v[226:229], v[100:103]
	v_mfma_f32_16x16x32_bf16 v[140:143], v[162:165], v[226:229], v[140:143]
	v_mfma_f32_16x16x32_bf16 v[150:153], v[214:217], v[226:229], v[150:153]
	v_mfma_f32_16x16x32_bf16 v[154:157], v[218:221], v[226:229], v[154:157]
	s_add_u32 s46, s0, 0xd80
	s_addc_u32 s47, s1, 0
	s_add_u32 s48, s14, 0xd80
	s_waitcnt vmcnt(0)
	s_barrier
	s_addc_u32 s49, s15, 0
	ds_read_b128 v[158:161], v7 offset:32768
	ds_read_b128 v[162:165], v6
	ds_read_b128 v[166:169], v7 offset:34816
	ds_read_b128 v[178:181], v6 offset:2048
	ds_read_b128 v[214:217], v7 offset:36864
	ds_read_b128 v[218:221], v7 offset:38912
	ds_read_b128 v[222:225], v6 offset:4096
	ds_read_b128 v[226:229], v6 offset:6144
	s_waitcnt lgkmcnt(6)
	v_mfma_f32_16x16x32_bf16 v[40:43], v[158:161], v[162:165], v[40:43]
	s_waitcnt lgkmcnt(5)
	v_mfma_f32_16x16x32_bf16 v[44:47], v[166:169], v[162:165], v[44:47]
	s_waitcnt lgkmcnt(4)
	v_mfma_f32_16x16x32_bf16 v[56:59], v[158:161], v[178:181], v[56:59]
	s_mov_b32 m0, s38
	v_mfma_f32_16x16x32_bf16 v[60:63], v[166:169], v[178:181], v[60:63]
	global_load_lds_dwordx4 v0, s[46:47]
	s_waitcnt lgkmcnt(3)
	v_mfma_f32_16x16x32_bf16 v[48:51], v[214:217], v[162:165], v[48:51]
	v_mfma_f32_16x16x32_bf16 v[64:67], v[214:217], v[178:181], v[64:67]
	s_waitcnt lgkmcnt(2)
	v_mfma_f32_16x16x32_bf16 v[174:177], v[218:221], v[162:165], v[174:177]
	ds_read_b128 v[162:165], v6 offset:8192
	v_mfma_f32_16x16x32_bf16 v[170:173], v[218:221], v[178:181], v[170:173]
	ds_read_b128 v[178:181], v6 offset:10240
	s_waitcnt lgkmcnt(3)
	s_mov_b32 m0, s37
	v_mfma_f32_16x16x32_bf16 v[72:75], v[158:161], v[222:225], v[72:75]
	global_load_lds_dwordx4 v0, s[48:49]
	v_mfma_f32_16x16x32_bf16 v[76:79], v[166:169], v[222:225], v[76:79]
	v_mfma_f32_16x16x32_bf16 v[80:83], v[214:217], v[222:225], v[80:83]
	v_mfma_f32_16x16x32_bf16 v[32:35], v[218:221], v[222:225], v[32:35]
	ds_read_b128 v[222:225], v6 offset:12288
	s_waitcnt lgkmcnt(3)
	v_mfma_f32_16x16x32_bf16 v[88:91], v[158:161], v[226:229], v[88:91]
	s_mov_b32 m0, s39
	v_mfma_f32_16x16x32_bf16 v[92:95], v[166:169], v[226:229], v[92:95]
	global_load_lds_dwordx4 v2, s[46:47]
	v_mfma_f32_16x16x32_bf16 v[96:99], v[214:217], v[226:229], v[96:99]
	v_mfma_f32_16x16x32_bf16 v[36:39], v[218:221], v[226:229], v[36:39]
	ds_read_b128 v[226:229], v6 offset:14336
	s_waitcnt lgkmcnt(3)
	v_mfma_f32_16x16x32_bf16 v[104:107], v[158:161], v[162:165], v[104:107]
	s_waitcnt lgkmcnt(2)
	v_mfma_f32_16x16x32_bf16 v[116:119], v[158:161], v[178:181], v[116:119]
	s_waitcnt lgkmcnt(1)
	s_mov_b32 m0, s40
	v_mfma_f32_16x16x32_bf16 v[128:131], v[158:161], v[222:225], v[128:131]
	global_load_lds_dwordx4 v2, s[48:49]
	s_waitcnt lgkmcnt(0)
	v_mfma_f32_16x16x32_bf16 v[100:103], v[158:161], v[226:229], v[100:103]
	ds_read_b128 v[158:161], v7 offset:33792
	v_mfma_f32_16x16x32_bf16 v[108:111], v[166:169], v[162:165], v[108:111]
	v_mfma_f32_16x16x32_bf16 v[120:123], v[166:169], v[178:181], v[120:123]
	v_mfma_f32_16x16x32_bf16 v[132:135], v[166:169], v[222:225], v[132:135]
	s_mov_b32 m0, s41
	v_mfma_f32_16x16x32_bf16 v[140:143], v[166:169], v[226:229], v[140:143]
	global_load_lds_dwordx4 v4, s[46:47]
	ds_read_b128 v[166:169], v6 offset:1024
	v_mfma_f32_16x16x32_bf16 v[112:115], v[214:217], v[162:165], v[112:115]
	v_mfma_f32_16x16x32_bf16 v[52:55], v[218:221], v[162:165], v[52:55]
	ds_read_b128 v[162:165], v7 offset:35840
	v_mfma_f32_16x16x32_bf16 v[124:127], v[214:217], v[178:181], v[124:127]
	v_mfma_f32_16x16x32_bf16 v[68:71], v[218:221], v[178:181], v[68:71]
	ds_read_b128 v[178:181], v6 offset:3072
	s_mov_b32 m0, s42
	v_mfma_f32_16x16x32_bf16 v[136:139], v[214:217], v[222:225], v[136:139]
	global_load_lds_dwordx4 v4, s[48:49]
	v_mfma_f32_16x16x32_bf16 v[84:87], v[218:221], v[222:225], v[84:87]
	ds_read_b128 v[222:225], v6 offset:5120
	v_mfma_f32_16x16x32_bf16 v[150:153], v[214:217], v[226:229], v[150:153]
	ds_read_b128 v[214:217], v7 offset:37888
	v_mfma_f32_16x16x32_bf16 v[154:157], v[218:221], v[226:229], v[154:157]
	ds_read_b128 v[218:221], v7 offset:39936
	ds_read_b128 v[226:229], v6 offset:7168
	s_waitcnt lgkmcnt(6)
	v_mfma_f32_16x16x32_bf16 v[40:43], v[158:161], v[166:169], v[40:43]
	s_waitcnt lgkmcnt(5)
	s_mov_b32 m0, s43
	v_mfma_f32_16x16x32_bf16 v[44:47], v[162:165], v[166:169], v[44:47]
	global_load_lds_dwordx4 v146, s[46:47]
	s_waitcnt lgkmcnt(4)
	v_mfma_f32_16x16x32_bf16 v[56:59], v[158:161], v[178:181], v[56:59]
	v_mfma_f32_16x16x32_bf16 v[60:63], v[162:165], v[178:181], v[60:63]
	s_waitcnt lgkmcnt(3)
	v_mfma_f32_16x16x32_bf16 v[72:75], v[158:161], v[222:225], v[72:75]
	v_mfma_f32_16x16x32_bf16 v[76:79], v[162:165], v[222:225], v[76:79]
	s_waitcnt lgkmcnt(2)
	s_mov_b32 m0, s44
	v_mfma_f32_16x16x32_bf16 v[48:51], v[214:217], v[166:169], v[48:51]
	global_load_lds_dwordx4 v146, s[48:49]
	s_waitcnt lgkmcnt(1)
	v_mfma_f32_16x16x32_bf16 v[174:177], v[218:221], v[166:169], v[174:177]
	ds_read_b128 v[166:169], v6 offset:9216
	v_mfma_f32_16x16x32_bf16 v[64:67], v[214:217], v[178:181], v[64:67]
	v_mfma_f32_16x16x32_bf16 v[170:173], v[218:221], v[178:181], v[170:173]
	ds_read_b128 v[178:181], v6 offset:11264
	v_mfma_f32_16x16x32_bf16 v[80:83], v[214:217], v[222:225], v[80:83]
	v_mfma_f32_16x16x32_bf16 v[32:35], v[218:221], v[222:225], v[32:35]
	ds_read_b128 v[222:225], v6 offset:13312
	s_waitcnt lgkmcnt(3)
	v_mfma_f32_16x16x32_bf16 v[88:91], v[158:161], v[226:229], v[88:91]
	v_mfma_f32_16x16x32_bf16 v[92:95], v[162:165], v[226:229], v[92:95]
	v_mfma_f32_16x16x32_bf16 v[96:99], v[214:217], v[226:229], v[96:99]
	v_mfma_f32_16x16x32_bf16 v[36:39], v[218:221], v[226:229], v[36:39]
	ds_read_b128 v[226:229], v6 offset:15360
	s_waitcnt lgkmcnt(3)
	v_mfma_f32_16x16x32_bf16 v[104:107], v[158:161], v[166:169], v[104:107]
	v_mfma_f32_16x16x32_bf16 v[108:111], v[162:165], v[166:169], v[108:111]
	v_mfma_f32_16x16x32_bf16 v[112:115], v[214:217], v[166:169], v[112:115]
	v_mfma_f32_16x16x32_bf16 v[52:55], v[218:221], v[166:169], v[52:55]
	s_waitcnt lgkmcnt(2)
	v_mfma_f32_16x16x32_bf16 v[116:119], v[158:161], v[178:181], v[116:119]
	v_mfma_f32_16x16x32_bf16 v[120:123], v[162:165], v[178:181], v[120:123]
	v_mfma_f32_16x16x32_bf16 v[124:127], v[214:217], v[178:181], v[124:127]
	v_mfma_f32_16x16x32_bf16 v[68:71], v[218:221], v[178:181], v[68:71]
	s_waitcnt lgkmcnt(1)
	v_mfma_f32_16x16x32_bf16 v[128:131], v[158:161], v[222:225], v[128:131]
	v_mfma_f32_16x16x32_bf16 v[132:135], v[162:165], v[222:225], v[132:135]
	v_mfma_f32_16x16x32_bf16 v[136:139], v[214:217], v[222:225], v[136:139]
	v_mfma_f32_16x16x32_bf16 v[84:87], v[218:221], v[222:225], v[84:87]
	s_waitcnt lgkmcnt(0)
	v_mfma_f32_16x16x32_bf16 v[100:103], v[158:161], v[226:229], v[100:103]
	v_mfma_f32_16x16x32_bf16 v[140:143], v[162:165], v[226:229], v[140:143]
	v_mfma_f32_16x16x32_bf16 v[150:153], v[214:217], v[226:229], v[150:153]
	v_mfma_f32_16x16x32_bf16 v[154:157], v[218:221], v[226:229], v[154:157]
	s_add_u32 s46, s0, 0xe00
	s_addc_u32 s47, s1, 0
	s_add_u32 s48, s14, 0xe00
	s_waitcnt vmcnt(0)
	s_barrier
	s_addc_u32 s49, s15, 0
	ds_read_b128 v[158:161], v8
	ds_read_b128 v[162:165], v12
	ds_read_b128 v[166:169], v9
	ds_read_b128 v[178:181], v13
	ds_read_b128 v[214:217], v11
	ds_read_b128 v[218:221], v10
	ds_read_b128 v[222:225], v14
	ds_read_b128 v[226:229], v15
	s_waitcnt lgkmcnt(6)
	v_mfma_f32_16x16x32_bf16 v[40:43], v[158:161], v[162:165], v[40:43]
	s_waitcnt lgkmcnt(5)
	v_mfma_f32_16x16x32_bf16 v[44:47], v[166:169], v[162:165], v[44:47]
	s_waitcnt lgkmcnt(4)
	v_mfma_f32_16x16x32_bf16 v[56:59], v[158:161], v[178:181], v[56:59]
	s_mov_b32 m0, s27
	v_mfma_f32_16x16x32_bf16 v[60:63], v[166:169], v[178:181], v[60:63]
	global_load_lds_dwordx4 v0, s[46:47]
	s_waitcnt lgkmcnt(3)
	v_mfma_f32_16x16x32_bf16 v[48:51], v[214:217], v[162:165], v[48:51]
	v_mfma_f32_16x16x32_bf16 v[64:67], v[214:217], v[178:181], v[64:67]
	s_waitcnt lgkmcnt(2)
	v_mfma_f32_16x16x32_bf16 v[174:177], v[218:221], v[162:165], v[174:177]
	ds_read_b128 v[162:165], v16
	v_mfma_f32_16x16x32_bf16 v[170:173], v[218:221], v[178:181], v[170:173]
	ds_read_b128 v[178:181], v17
	s_waitcnt lgkmcnt(3)
	s_mov_b32 m0, s28
	v_mfma_f32_16x16x32_bf16 v[72:75], v[158:161], v[222:225], v[72:75]
	global_load_lds_dwordx4 v0, s[48:49]
	v_mfma_f32_16x16x32_bf16 v[76:79], v[166:169], v[222:225], v[76:79]
	v_mfma_f32_16x16x32_bf16 v[80:83], v[214:217], v[222:225], v[80:83]
	v_mfma_f32_16x16x32_bf16 v[32:35], v[218:221], v[222:225], v[32:35]
	ds_read_b128 v[222:225], v18
	s_waitcnt lgkmcnt(3)
	v_mfma_f32_16x16x32_bf16 v[88:91], v[158:161], v[226:229], v[88:91]
	s_mov_b32 m0, s29
	v_mfma_f32_16x16x32_bf16 v[92:95], v[166:169], v[226:229], v[92:95]
	global_load_lds_dwordx4 v2, s[46:47]
	v_mfma_f32_16x16x32_bf16 v[96:99], v[214:217], v[226:229], v[96:99]
	v_mfma_f32_16x16x32_bf16 v[36:39], v[218:221], v[226:229], v[36:39]
	ds_read_b128 v[226:229], v19
	s_waitcnt lgkmcnt(3)
	v_mfma_f32_16x16x32_bf16 v[104:107], v[158:161], v[162:165], v[104:107]
	s_waitcnt lgkmcnt(2)
	v_mfma_f32_16x16x32_bf16 v[116:119], v[158:161], v[178:181], v[116:119]
	s_waitcnt lgkmcnt(1)
	s_mov_b32 m0, s30
	v_mfma_f32_16x16x32_bf16 v[128:131], v[158:161], v[222:225], v[128:131]
	global_load_lds_dwordx4 v2, s[48:49]
	s_waitcnt lgkmcnt(0)
	v_mfma_f32_16x16x32_bf16 v[100:103], v[158:161], v[226:229], v[100:103]
	ds_read_b128 v[158:161], v20
	v_mfma_f32_16x16x32_bf16 v[108:111], v[166:169], v[162:165], v[108:111]
	v_mfma_f32_16x16x32_bf16 v[120:123], v[166:169], v[178:181], v[120:123]
	v_mfma_f32_16x16x32_bf16 v[132:135], v[166:169], v[222:225], v[132:135]
	s_mov_b32 m0, s31
	v_mfma_f32_16x16x32_bf16 v[140:143], v[166:169], v[226:229], v[140:143]
	global_load_lds_dwordx4 v4, s[46:47]
	ds_read_b128 v[166:169], v24
	v_mfma_f32_16x16x32_bf16 v[112:115], v[214:217], v[162:165], v[112:115]
	v_mfma_f32_16x16x32_bf16 v[52:55], v[218:221], v[162:165], v[52:55]
	ds_read_b128 v[162:165], v21
	v_mfma_f32_16x16x32_bf16 v[124:127], v[214:217], v[178:181], v[124:127]
	v_mfma_f32_16x16x32_bf16 v[68:71], v[218:221], v[178:181], v[68:71]
	ds_read_b128 v[178:181], v25
	s_mov_b32 m0, s34
	v_mfma_f32_16x16x32_bf16 v[136:139], v[214:217], v[222:225], v[136:139]
	global_load_lds_dwordx4 v4, s[48:49]
	v_mfma_f32_16x16x32_bf16 v[84:87], v[218:221], v[222:225], v[84:87]
	ds_read_b128 v[222:225], v26
	v_mfma_f32_16x16x32_bf16 v[150:153], v[214:217], v[226:229], v[150:153]
	ds_read_b128 v[214:217], v23
	v_mfma_f32_16x16x32_bf16 v[154:157], v[218:221], v[226:229], v[154:157]
	ds_read_b128 v[218:221], v22
	ds_read_b128 v[226:229], v27
	s_waitcnt lgkmcnt(6)
	v_mfma_f32_16x16x32_bf16 v[40:43], v[158:161], v[166:169], v[40:43]
	s_waitcnt lgkmcnt(5)
	s_mov_b32 m0, s35
	v_mfma_f32_16x16x32_bf16 v[44:47], v[162:165], v[166:169], v[44:47]
	global_load_lds_dwordx4 v146, s[46:47]
	s_waitcnt lgkmcnt(4)
	v_mfma_f32_16x16x32_bf16 v[56:59], v[158:161], v[178:181], v[56:59]
	v_mfma_f32_16x16x32_bf16 v[60:63], v[162:165], v[178:181], v[60:63]
	s_waitcnt lgkmcnt(3)
	v_mfma_f32_16x16x32_bf16 v[72:75], v[158:161], v[222:225], v[72:75]
	v_mfma_f32_16x16x32_bf16 v[76:79], v[162:165], v[222:225], v[76:79]
	s_waitcnt lgkmcnt(2)
	s_mov_b32 m0, s36
	v_mfma_f32_16x16x32_bf16 v[48:51], v[214:217], v[166:169], v[48:51]
	global_load_lds_dwordx4 v146, s[48:49]
	s_waitcnt lgkmcnt(1)
	v_mfma_f32_16x16x32_bf16 v[174:177], v[218:221], v[166:169], v[174:177]
	ds_read_b128 v[166:169], v28
	v_mfma_f32_16x16x32_bf16 v[64:67], v[214:217], v[178:181], v[64:67]
	v_mfma_f32_16x16x32_bf16 v[170:173], v[218:221], v[178:181], v[170:173]
	ds_read_b128 v[178:181], v29
	v_mfma_f32_16x16x32_bf16 v[80:83], v[214:217], v[222:225], v[80:83]
	v_mfma_f32_16x16x32_bf16 v[32:35], v[218:221], v[222:225], v[32:35]
	ds_read_b128 v[222:225], v30
	s_waitcnt lgkmcnt(3)
	v_mfma_f32_16x16x32_bf16 v[88:91], v[158:161], v[226:229], v[88:91]
	v_mfma_f32_16x16x32_bf16 v[92:95], v[162:165], v[226:229], v[92:95]
	v_mfma_f32_16x16x32_bf16 v[96:99], v[214:217], v[226:229], v[96:99]
	v_mfma_f32_16x16x32_bf16 v[36:39], v[218:221], v[226:229], v[36:39]
	ds_read_b128 v[226:229], v31
	s_waitcnt lgkmcnt(3)
	v_mfma_f32_16x16x32_bf16 v[104:107], v[158:161], v[166:169], v[104:107]
	v_mfma_f32_16x16x32_bf16 v[108:111], v[162:165], v[166:169], v[108:111]
	v_mfma_f32_16x16x32_bf16 v[112:115], v[214:217], v[166:169], v[112:115]
	v_mfma_f32_16x16x32_bf16 v[52:55], v[218:221], v[166:169], v[52:55]
	s_waitcnt lgkmcnt(2)
	v_mfma_f32_16x16x32_bf16 v[116:119], v[158:161], v[178:181], v[116:119]
	v_mfma_f32_16x16x32_bf16 v[120:123], v[162:165], v[178:181], v[120:123]
	v_mfma_f32_16x16x32_bf16 v[124:127], v[214:217], v[178:181], v[124:127]
	v_mfma_f32_16x16x32_bf16 v[68:71], v[218:221], v[178:181], v[68:71]
	s_waitcnt lgkmcnt(1)
	v_mfma_f32_16x16x32_bf16 v[128:131], v[158:161], v[222:225], v[128:131]
	v_mfma_f32_16x16x32_bf16 v[132:135], v[162:165], v[222:225], v[132:135]
	v_mfma_f32_16x16x32_bf16 v[136:139], v[214:217], v[222:225], v[136:139]
	v_mfma_f32_16x16x32_bf16 v[84:87], v[218:221], v[222:225], v[84:87]
	s_waitcnt lgkmcnt(0)
	v_mfma_f32_16x16x32_bf16 v[100:103], v[158:161], v[226:229], v[100:103]
	v_mfma_f32_16x16x32_bf16 v[140:143], v[162:165], v[226:229], v[140:143]
	v_mfma_f32_16x16x32_bf16 v[150:153], v[214:217], v[226:229], v[150:153]
	v_mfma_f32_16x16x32_bf16 v[154:157], v[218:221], v[226:229], v[154:157]
	s_add_u32 s46, s0, 0xe80
	s_addc_u32 s47, s1, 0
	s_add_u32 s48, s14, 0xe80
	s_waitcnt vmcnt(0)
	s_barrier
	s_addc_u32 s49, s15, 0
	ds_read_b128 v[158:161], v7 offset:32768
	ds_read_b128 v[162:165], v6
	ds_read_b128 v[166:169], v7 offset:34816
	ds_read_b128 v[178:181], v6 offset:2048
	ds_read_b128 v[214:217], v7 offset:36864
	ds_read_b128 v[218:221], v7 offset:38912
	ds_read_b128 v[222:225], v6 offset:4096
	ds_read_b128 v[226:229], v6 offset:6144
	s_waitcnt lgkmcnt(6)
	v_mfma_f32_16x16x32_bf16 v[40:43], v[158:161], v[162:165], v[40:43]
	s_waitcnt lgkmcnt(5)
	v_mfma_f32_16x16x32_bf16 v[44:47], v[166:169], v[162:165], v[44:47]
	s_waitcnt lgkmcnt(4)
	v_mfma_f32_16x16x32_bf16 v[56:59], v[158:161], v[178:181], v[56:59]
	s_mov_b32 m0, s38
	v_mfma_f32_16x16x32_bf16 v[60:63], v[166:169], v[178:181], v[60:63]
	global_load_lds_dwordx4 v0, s[46:47]
	s_waitcnt lgkmcnt(3)
	v_mfma_f32_16x16x32_bf16 v[48:51], v[214:217], v[162:165], v[48:51]
	v_mfma_f32_16x16x32_bf16 v[64:67], v[214:217], v[178:181], v[64:67]
	s_waitcnt lgkmcnt(2)
	v_mfma_f32_16x16x32_bf16 v[174:177], v[218:221], v[162:165], v[174:177]
	ds_read_b128 v[162:165], v6 offset:8192
	v_mfma_f32_16x16x32_bf16 v[170:173], v[218:221], v[178:181], v[170:173]
	ds_read_b128 v[178:181], v6 offset:10240
	s_waitcnt lgkmcnt(3)
	s_mov_b32 m0, s37
	v_mfma_f32_16x16x32_bf16 v[72:75], v[158:161], v[222:225], v[72:75]
	global_load_lds_dwordx4 v0, s[48:49]
	v_mfma_f32_16x16x32_bf16 v[76:79], v[166:169], v[222:225], v[76:79]
	v_mfma_f32_16x16x32_bf16 v[80:83], v[214:217], v[222:225], v[80:83]
	v_mfma_f32_16x16x32_bf16 v[32:35], v[218:221], v[222:225], v[32:35]
	ds_read_b128 v[222:225], v6 offset:12288
	s_waitcnt lgkmcnt(3)
	v_mfma_f32_16x16x32_bf16 v[88:91], v[158:161], v[226:229], v[88:91]
	s_mov_b32 m0, s39
	v_mfma_f32_16x16x32_bf16 v[92:95], v[166:169], v[226:229], v[92:95]
	global_load_lds_dwordx4 v2, s[46:47]
	v_mfma_f32_16x16x32_bf16 v[96:99], v[214:217], v[226:229], v[96:99]
	v_mfma_f32_16x16x32_bf16 v[36:39], v[218:221], v[226:229], v[36:39]
	ds_read_b128 v[226:229], v6 offset:14336
	s_waitcnt lgkmcnt(3)
	v_mfma_f32_16x16x32_bf16 v[104:107], v[158:161], v[162:165], v[104:107]
	s_waitcnt lgkmcnt(2)
	v_mfma_f32_16x16x32_bf16 v[116:119], v[158:161], v[178:181], v[116:119]
	s_waitcnt lgkmcnt(1)
	s_mov_b32 m0, s40
	v_mfma_f32_16x16x32_bf16 v[128:131], v[158:161], v[222:225], v[128:131]
	global_load_lds_dwordx4 v2, s[48:49]
	s_waitcnt lgkmcnt(0)
	v_mfma_f32_16x16x32_bf16 v[100:103], v[158:161], v[226:229], v[100:103]
	ds_read_b128 v[158:161], v7 offset:33792
	v_mfma_f32_16x16x32_bf16 v[108:111], v[166:169], v[162:165], v[108:111]
	v_mfma_f32_16x16x32_bf16 v[120:123], v[166:169], v[178:181], v[120:123]
	v_mfma_f32_16x16x32_bf16 v[132:135], v[166:169], v[222:225], v[132:135]
	s_mov_b32 m0, s41
	v_mfma_f32_16x16x32_bf16 v[140:143], v[166:169], v[226:229], v[140:143]
	global_load_lds_dwordx4 v4, s[46:47]
	ds_read_b128 v[166:169], v6 offset:1024
	v_mfma_f32_16x16x32_bf16 v[112:115], v[214:217], v[162:165], v[112:115]
	v_mfma_f32_16x16x32_bf16 v[52:55], v[218:221], v[162:165], v[52:55]
	ds_read_b128 v[162:165], v7 offset:35840
	v_mfma_f32_16x16x32_bf16 v[124:127], v[214:217], v[178:181], v[124:127]
	v_mfma_f32_16x16x32_bf16 v[68:71], v[218:221], v[178:181], v[68:71]
	ds_read_b128 v[178:181], v6 offset:3072
	s_mov_b32 m0, s42
	v_mfma_f32_16x16x32_bf16 v[136:139], v[214:217], v[222:225], v[136:139]
	global_load_lds_dwordx4 v4, s[48:49]
	v_mfma_f32_16x16x32_bf16 v[84:87], v[218:221], v[222:225], v[84:87]
	ds_read_b128 v[222:225], v6 offset:5120
	v_mfma_f32_16x16x32_bf16 v[150:153], v[214:217], v[226:229], v[150:153]
	ds_read_b128 v[214:217], v7 offset:37888
	v_mfma_f32_16x16x32_bf16 v[154:157], v[218:221], v[226:229], v[154:157]
	ds_read_b128 v[218:221], v7 offset:39936
	ds_read_b128 v[226:229], v6 offset:7168
	s_waitcnt lgkmcnt(6)
	v_mfma_f32_16x16x32_bf16 v[40:43], v[158:161], v[166:169], v[40:43]
	s_waitcnt lgkmcnt(5)
	s_mov_b32 m0, s43
	v_mfma_f32_16x16x32_bf16 v[44:47], v[162:165], v[166:169], v[44:47]
	global_load_lds_dwordx4 v146, s[46:47]
	s_waitcnt lgkmcnt(4)
	v_mfma_f32_16x16x32_bf16 v[56:59], v[158:161], v[178:181], v[56:59]
	v_mfma_f32_16x16x32_bf16 v[60:63], v[162:165], v[178:181], v[60:63]
	s_waitcnt lgkmcnt(3)
	v_mfma_f32_16x16x32_bf16 v[72:75], v[158:161], v[222:225], v[72:75]
	v_mfma_f32_16x16x32_bf16 v[76:79], v[162:165], v[222:225], v[76:79]
	s_waitcnt lgkmcnt(2)
	s_mov_b32 m0, s44
	v_mfma_f32_16x16x32_bf16 v[48:51], v[214:217], v[166:169], v[48:51]
	global_load_lds_dwordx4 v146, s[48:49]
	s_waitcnt lgkmcnt(1)
	v_mfma_f32_16x16x32_bf16 v[174:177], v[218:221], v[166:169], v[174:177]
	ds_read_b128 v[166:169], v6 offset:9216
	v_mfma_f32_16x16x32_bf16 v[64:67], v[214:217], v[178:181], v[64:67]
	v_mfma_f32_16x16x32_bf16 v[170:173], v[218:221], v[178:181], v[170:173]
	ds_read_b128 v[178:181], v6 offset:11264
	v_mfma_f32_16x16x32_bf16 v[80:83], v[214:217], v[222:225], v[80:83]
	v_mfma_f32_16x16x32_bf16 v[32:35], v[218:221], v[222:225], v[32:35]
	ds_read_b128 v[222:225], v6 offset:13312
	s_waitcnt lgkmcnt(3)
	v_mfma_f32_16x16x32_bf16 v[88:91], v[158:161], v[226:229], v[88:91]
	v_mfma_f32_16x16x32_bf16 v[92:95], v[162:165], v[226:229], v[92:95]
	v_mfma_f32_16x16x32_bf16 v[96:99], v[214:217], v[226:229], v[96:99]
	v_mfma_f32_16x16x32_bf16 v[36:39], v[218:221], v[226:229], v[36:39]
	ds_read_b128 v[226:229], v6 offset:15360
	s_waitcnt lgkmcnt(3)
	v_mfma_f32_16x16x32_bf16 v[104:107], v[158:161], v[166:169], v[104:107]
	v_mfma_f32_16x16x32_bf16 v[108:111], v[162:165], v[166:169], v[108:111]
	v_mfma_f32_16x16x32_bf16 v[112:115], v[214:217], v[166:169], v[112:115]
	v_mfma_f32_16x16x32_bf16 v[52:55], v[218:221], v[166:169], v[52:55]
	s_waitcnt lgkmcnt(2)
	v_mfma_f32_16x16x32_bf16 v[116:119], v[158:161], v[178:181], v[116:119]
	v_mfma_f32_16x16x32_bf16 v[120:123], v[162:165], v[178:181], v[120:123]
	v_mfma_f32_16x16x32_bf16 v[124:127], v[214:217], v[178:181], v[124:127]
	v_mfma_f32_16x16x32_bf16 v[68:71], v[218:221], v[178:181], v[68:71]
	s_waitcnt lgkmcnt(1)
	v_mfma_f32_16x16x32_bf16 v[128:131], v[158:161], v[222:225], v[128:131]
	v_mfma_f32_16x16x32_bf16 v[132:135], v[162:165], v[222:225], v[132:135]
	v_mfma_f32_16x16x32_bf16 v[136:139], v[214:217], v[222:225], v[136:139]
	v_mfma_f32_16x16x32_bf16 v[84:87], v[218:221], v[222:225], v[84:87]
	s_waitcnt lgkmcnt(0)
	v_mfma_f32_16x16x32_bf16 v[100:103], v[158:161], v[226:229], v[100:103]
	v_mfma_f32_16x16x32_bf16 v[140:143], v[162:165], v[226:229], v[140:143]
	v_mfma_f32_16x16x32_bf16 v[150:153], v[214:217], v[226:229], v[150:153]
	v_mfma_f32_16x16x32_bf16 v[154:157], v[218:221], v[226:229], v[154:157]
	s_add_u32 s46, s0, 0xf00
	s_addc_u32 s47, s1, 0
	s_add_u32 s48, s14, 0xf00
	s_waitcnt vmcnt(0)
	s_barrier
	s_addc_u32 s49, s15, 0
	ds_read_b128 v[158:161], v8
	ds_read_b128 v[162:165], v12
	ds_read_b128 v[166:169], v9
	ds_read_b128 v[178:181], v13
	ds_read_b128 v[214:217], v11
	ds_read_b128 v[218:221], v10
	ds_read_b128 v[222:225], v14
	ds_read_b128 v[226:229], v15
	s_waitcnt lgkmcnt(6)
	v_mfma_f32_16x16x32_bf16 v[40:43], v[158:161], v[162:165], v[40:43]
	s_waitcnt lgkmcnt(5)
	v_mfma_f32_16x16x32_bf16 v[44:47], v[166:169], v[162:165], v[44:47]
	s_waitcnt lgkmcnt(4)
	v_mfma_f32_16x16x32_bf16 v[56:59], v[158:161], v[178:181], v[56:59]
	s_mov_b32 m0, s27
	v_mfma_f32_16x16x32_bf16 v[60:63], v[166:169], v[178:181], v[60:63]
	global_load_lds_dwordx4 v0, s[46:47]
	s_waitcnt lgkmcnt(3)
	v_mfma_f32_16x16x32_bf16 v[48:51], v[214:217], v[162:165], v[48:51]
	v_mfma_f32_16x16x32_bf16 v[64:67], v[214:217], v[178:181], v[64:67]
	s_waitcnt lgkmcnt(2)
	v_mfma_f32_16x16x32_bf16 v[174:177], v[218:221], v[162:165], v[174:177]
	ds_read_b128 v[162:165], v16
	v_mfma_f32_16x16x32_bf16 v[170:173], v[218:221], v[178:181], v[170:173]
	ds_read_b128 v[178:181], v17
	s_waitcnt lgkmcnt(3)
	s_mov_b32 m0, s28
	v_mfma_f32_16x16x32_bf16 v[72:75], v[158:161], v[222:225], v[72:75]
	global_load_lds_dwordx4 v0, s[48:49]
	v_mfma_f32_16x16x32_bf16 v[76:79], v[166:169], v[222:225], v[76:79]
	v_mfma_f32_16x16x32_bf16 v[80:83], v[214:217], v[222:225], v[80:83]
	v_mfma_f32_16x16x32_bf16 v[32:35], v[218:221], v[222:225], v[32:35]
	ds_read_b128 v[222:225], v18
	s_waitcnt lgkmcnt(3)
	v_mfma_f32_16x16x32_bf16 v[88:91], v[158:161], v[226:229], v[88:91]
	s_mov_b32 m0, s29
	v_mfma_f32_16x16x32_bf16 v[92:95], v[166:169], v[226:229], v[92:95]
	global_load_lds_dwordx4 v2, s[46:47]
	v_mfma_f32_16x16x32_bf16 v[96:99], v[214:217], v[226:229], v[96:99]
	v_mfma_f32_16x16x32_bf16 v[36:39], v[218:221], v[226:229], v[36:39]
	ds_read_b128 v[226:229], v19
	s_waitcnt lgkmcnt(3)
	v_mfma_f32_16x16x32_bf16 v[104:107], v[158:161], v[162:165], v[104:107]
	s_waitcnt lgkmcnt(2)
	v_mfma_f32_16x16x32_bf16 v[116:119], v[158:161], v[178:181], v[116:119]
	s_waitcnt lgkmcnt(1)
	s_mov_b32 m0, s30
	v_mfma_f32_16x16x32_bf16 v[128:131], v[158:161], v[222:225], v[128:131]
	global_load_lds_dwordx4 v2, s[48:49]
	s_waitcnt lgkmcnt(0)
	v_mfma_f32_16x16x32_bf16 v[100:103], v[158:161], v[226:229], v[100:103]
	ds_read_b128 v[158:161], v20
	v_mfma_f32_16x16x32_bf16 v[108:111], v[166:169], v[162:165], v[108:111]
	v_mfma_f32_16x16x32_bf16 v[120:123], v[166:169], v[178:181], v[120:123]
	v_mfma_f32_16x16x32_bf16 v[132:135], v[166:169], v[222:225], v[132:135]
	s_mov_b32 m0, s31
	v_mfma_f32_16x16x32_bf16 v[140:143], v[166:169], v[226:229], v[140:143]
	global_load_lds_dwordx4 v4, s[46:47]
	ds_read_b128 v[166:169], v24
	v_mfma_f32_16x16x32_bf16 v[112:115], v[214:217], v[162:165], v[112:115]
	v_mfma_f32_16x16x32_bf16 v[52:55], v[218:221], v[162:165], v[52:55]
	ds_read_b128 v[162:165], v21
	v_mfma_f32_16x16x32_bf16 v[124:127], v[214:217], v[178:181], v[124:127]
	v_mfma_f32_16x16x32_bf16 v[68:71], v[218:221], v[178:181], v[68:71]
	ds_read_b128 v[178:181], v25
	s_mov_b32 m0, s34
	v_mfma_f32_16x16x32_bf16 v[136:139], v[214:217], v[222:225], v[136:139]
	global_load_lds_dwordx4 v4, s[48:49]
	v_mfma_f32_16x16x32_bf16 v[84:87], v[218:221], v[222:225], v[84:87]
	ds_read_b128 v[222:225], v26
	v_mfma_f32_16x16x32_bf16 v[150:153], v[214:217], v[226:229], v[150:153]
	ds_read_b128 v[214:217], v23
	v_mfma_f32_16x16x32_bf16 v[154:157], v[218:221], v[226:229], v[154:157]
	ds_read_b128 v[218:221], v22
	ds_read_b128 v[226:229], v27
	s_waitcnt lgkmcnt(6)
	v_mfma_f32_16x16x32_bf16 v[40:43], v[158:161], v[166:169], v[40:43]
	s_waitcnt lgkmcnt(5)
	s_mov_b32 m0, s35
	v_mfma_f32_16x16x32_bf16 v[44:47], v[162:165], v[166:169], v[44:47]
	global_load_lds_dwordx4 v146, s[46:47]
	s_waitcnt lgkmcnt(4)
	v_mfma_f32_16x16x32_bf16 v[56:59], v[158:161], v[178:181], v[56:59]
	v_mfma_f32_16x16x32_bf16 v[60:63], v[162:165], v[178:181], v[60:63]
	s_waitcnt lgkmcnt(3)
	v_mfma_f32_16x16x32_bf16 v[72:75], v[158:161], v[222:225], v[72:75]
	v_mfma_f32_16x16x32_bf16 v[76:79], v[162:165], v[222:225], v[76:79]
	s_waitcnt lgkmcnt(2)
	s_mov_b32 m0, s36
	v_mfma_f32_16x16x32_bf16 v[48:51], v[214:217], v[166:169], v[48:51]
	global_load_lds_dwordx4 v146, s[48:49]
	s_waitcnt lgkmcnt(1)
	v_mfma_f32_16x16x32_bf16 v[174:177], v[218:221], v[166:169], v[174:177]
	ds_read_b128 v[166:169], v28
	v_mfma_f32_16x16x32_bf16 v[64:67], v[214:217], v[178:181], v[64:67]
	v_mfma_f32_16x16x32_bf16 v[170:173], v[218:221], v[178:181], v[170:173]
	ds_read_b128 v[178:181], v29
	v_mfma_f32_16x16x32_bf16 v[80:83], v[214:217], v[222:225], v[80:83]
	v_mfma_f32_16x16x32_bf16 v[32:35], v[218:221], v[222:225], v[32:35]
	ds_read_b128 v[222:225], v30
	s_waitcnt lgkmcnt(3)
	v_mfma_f32_16x16x32_bf16 v[88:91], v[158:161], v[226:229], v[88:91]
	v_mfma_f32_16x16x32_bf16 v[92:95], v[162:165], v[226:229], v[92:95]
	v_mfma_f32_16x16x32_bf16 v[96:99], v[214:217], v[226:229], v[96:99]
	v_mfma_f32_16x16x32_bf16 v[36:39], v[218:221], v[226:229], v[36:39]
	ds_read_b128 v[226:229], v31
	s_waitcnt lgkmcnt(3)
	v_mfma_f32_16x16x32_bf16 v[104:107], v[158:161], v[166:169], v[104:107]
	v_mfma_f32_16x16x32_bf16 v[108:111], v[162:165], v[166:169], v[108:111]
	v_mfma_f32_16x16x32_bf16 v[112:115], v[214:217], v[166:169], v[112:115]
	v_mfma_f32_16x16x32_bf16 v[52:55], v[218:221], v[166:169], v[52:55]
	s_waitcnt lgkmcnt(2)
	v_mfma_f32_16x16x32_bf16 v[116:119], v[158:161], v[178:181], v[116:119]
	v_mfma_f32_16x16x32_bf16 v[120:123], v[162:165], v[178:181], v[120:123]
	v_mfma_f32_16x16x32_bf16 v[124:127], v[214:217], v[178:181], v[124:127]
	v_mfma_f32_16x16x32_bf16 v[68:71], v[218:221], v[178:181], v[68:71]
	s_waitcnt lgkmcnt(1)
	v_mfma_f32_16x16x32_bf16 v[128:131], v[158:161], v[222:225], v[128:131]
	v_mfma_f32_16x16x32_bf16 v[132:135], v[162:165], v[222:225], v[132:135]
	v_mfma_f32_16x16x32_bf16 v[136:139], v[214:217], v[222:225], v[136:139]
	v_mfma_f32_16x16x32_bf16 v[84:87], v[218:221], v[222:225], v[84:87]
	s_waitcnt lgkmcnt(0)
	v_mfma_f32_16x16x32_bf16 v[100:103], v[158:161], v[226:229], v[100:103]
	v_mfma_f32_16x16x32_bf16 v[140:143], v[162:165], v[226:229], v[140:143]
	v_mfma_f32_16x16x32_bf16 v[150:153], v[214:217], v[226:229], v[150:153]
	v_mfma_f32_16x16x32_bf16 v[154:157], v[218:221], v[226:229], v[154:157]
	s_add_u32 s46, s0, 0xf80
	s_addc_u32 s47, s1, 0
	s_add_u32 s48, s14, 0xf80
	s_waitcnt vmcnt(0)
	s_barrier
	s_addc_u32 s49, s15, 0
	ds_read_b128 v[158:161], v7 offset:32768
	ds_read_b128 v[162:165], v6
	ds_read_b128 v[166:169], v7 offset:34816
	ds_read_b128 v[178:181], v6 offset:2048
	ds_read_b128 v[214:217], v7 offset:36864
	ds_read_b128 v[218:221], v7 offset:38912
	ds_read_b128 v[222:225], v6 offset:4096
	ds_read_b128 v[226:229], v6 offset:6144
	s_waitcnt lgkmcnt(6)
	v_mfma_f32_16x16x32_bf16 v[40:43], v[158:161], v[162:165], v[40:43]
	s_waitcnt lgkmcnt(5)
	v_mfma_f32_16x16x32_bf16 v[44:47], v[166:169], v[162:165], v[44:47]
	s_waitcnt lgkmcnt(4)
	v_mfma_f32_16x16x32_bf16 v[56:59], v[158:161], v[178:181], v[56:59]
	s_mov_b32 m0, s38
	v_mfma_f32_16x16x32_bf16 v[60:63], v[166:169], v[178:181], v[60:63]
	global_load_lds_dwordx4 v0, s[46:47]
	s_waitcnt lgkmcnt(3)
	v_mfma_f32_16x16x32_bf16 v[48:51], v[214:217], v[162:165], v[48:51]
	v_mfma_f32_16x16x32_bf16 v[64:67], v[214:217], v[178:181], v[64:67]
	s_waitcnt lgkmcnt(2)
	v_mfma_f32_16x16x32_bf16 v[174:177], v[218:221], v[162:165], v[174:177]
	ds_read_b128 v[162:165], v6 offset:8192
	v_mfma_f32_16x16x32_bf16 v[170:173], v[218:221], v[178:181], v[170:173]
	ds_read_b128 v[178:181], v6 offset:10240
	s_waitcnt lgkmcnt(3)
	s_mov_b32 m0, s37
	v_mfma_f32_16x16x32_bf16 v[72:75], v[158:161], v[222:225], v[72:75]
	global_load_lds_dwordx4 v0, s[48:49]
	v_mfma_f32_16x16x32_bf16 v[76:79], v[166:169], v[222:225], v[76:79]
	v_mfma_f32_16x16x32_bf16 v[80:83], v[214:217], v[222:225], v[80:83]
	v_mfma_f32_16x16x32_bf16 v[32:35], v[218:221], v[222:225], v[32:35]
	ds_read_b128 v[222:225], v6 offset:12288
	s_waitcnt lgkmcnt(3)
	v_mfma_f32_16x16x32_bf16 v[88:91], v[158:161], v[226:229], v[88:91]
	s_mov_b32 m0, s39
	v_mfma_f32_16x16x32_bf16 v[92:95], v[166:169], v[226:229], v[92:95]
	global_load_lds_dwordx4 v2, s[46:47]
	v_mfma_f32_16x16x32_bf16 v[96:99], v[214:217], v[226:229], v[96:99]
	v_mfma_f32_16x16x32_bf16 v[36:39], v[218:221], v[226:229], v[36:39]
	ds_read_b128 v[226:229], v6 offset:14336
	s_waitcnt lgkmcnt(3)
	v_mfma_f32_16x16x32_bf16 v[104:107], v[158:161], v[162:165], v[104:107]
	s_waitcnt lgkmcnt(2)
	v_mfma_f32_16x16x32_bf16 v[116:119], v[158:161], v[178:181], v[116:119]
	s_waitcnt lgkmcnt(1)
	s_mov_b32 m0, s40
	v_mfma_f32_16x16x32_bf16 v[128:131], v[158:161], v[222:225], v[128:131]
	global_load_lds_dwordx4 v2, s[48:49]
	s_waitcnt lgkmcnt(0)
	v_mfma_f32_16x16x32_bf16 v[100:103], v[158:161], v[226:229], v[100:103]
	ds_read_b128 v[158:161], v7 offset:33792
	v_mfma_f32_16x16x32_bf16 v[108:111], v[166:169], v[162:165], v[108:111]
	v_mfma_f32_16x16x32_bf16 v[120:123], v[166:169], v[178:181], v[120:123]
	v_mfma_f32_16x16x32_bf16 v[132:135], v[166:169], v[222:225], v[132:135]
	s_mov_b32 m0, s41
	v_mfma_f32_16x16x32_bf16 v[140:143], v[166:169], v[226:229], v[140:143]
	global_load_lds_dwordx4 v4, s[46:47]
	ds_read_b128 v[166:169], v6 offset:1024
	v_mfma_f32_16x16x32_bf16 v[112:115], v[214:217], v[162:165], v[112:115]
	v_mfma_f32_16x16x32_bf16 v[52:55], v[218:221], v[162:165], v[52:55]
	ds_read_b128 v[162:165], v7 offset:35840
	v_mfma_f32_16x16x32_bf16 v[124:127], v[214:217], v[178:181], v[124:127]
	v_mfma_f32_16x16x32_bf16 v[68:71], v[218:221], v[178:181], v[68:71]
	ds_read_b128 v[178:181], v6 offset:3072
	s_mov_b32 m0, s42
	v_mfma_f32_16x16x32_bf16 v[136:139], v[214:217], v[222:225], v[136:139]
	global_load_lds_dwordx4 v4, s[48:49]
	v_mfma_f32_16x16x32_bf16 v[84:87], v[218:221], v[222:225], v[84:87]
	ds_read_b128 v[222:225], v6 offset:5120
	v_mfma_f32_16x16x32_bf16 v[150:153], v[214:217], v[226:229], v[150:153]
	ds_read_b128 v[214:217], v7 offset:37888
	v_mfma_f32_16x16x32_bf16 v[154:157], v[218:221], v[226:229], v[154:157]
	ds_read_b128 v[218:221], v7 offset:39936
	ds_read_b128 v[226:229], v6 offset:7168
	s_waitcnt lgkmcnt(6)
	v_mfma_f32_16x16x32_bf16 v[40:43], v[158:161], v[166:169], v[40:43]
	s_waitcnt lgkmcnt(5)
	s_mov_b32 m0, s43
	v_mfma_f32_16x16x32_bf16 v[44:47], v[162:165], v[166:169], v[44:47]
	global_load_lds_dwordx4 v146, s[46:47]
	s_waitcnt lgkmcnt(4)
	v_mfma_f32_16x16x32_bf16 v[56:59], v[158:161], v[178:181], v[56:59]
	v_mfma_f32_16x16x32_bf16 v[60:63], v[162:165], v[178:181], v[60:63]
	s_waitcnt lgkmcnt(3)
	v_mfma_f32_16x16x32_bf16 v[72:75], v[158:161], v[222:225], v[72:75]
	v_mfma_f32_16x16x32_bf16 v[76:79], v[162:165], v[222:225], v[76:79]
	s_waitcnt lgkmcnt(2)
	s_mov_b32 m0, s44
	v_mfma_f32_16x16x32_bf16 v[48:51], v[214:217], v[166:169], v[48:51]
	global_load_lds_dwordx4 v146, s[48:49]
	s_waitcnt lgkmcnt(1)
	v_mfma_f32_16x16x32_bf16 v[174:177], v[218:221], v[166:169], v[174:177]
	ds_read_b128 v[166:169], v6 offset:9216
	v_mfma_f32_16x16x32_bf16 v[64:67], v[214:217], v[178:181], v[64:67]
	v_mfma_f32_16x16x32_bf16 v[170:173], v[218:221], v[178:181], v[170:173]
	ds_read_b128 v[178:181], v6 offset:11264
	v_mfma_f32_16x16x32_bf16 v[80:83], v[214:217], v[222:225], v[80:83]
	v_mfma_f32_16x16x32_bf16 v[32:35], v[218:221], v[222:225], v[32:35]
	ds_read_b128 v[222:225], v6 offset:13312
	s_waitcnt lgkmcnt(3)
	v_mfma_f32_16x16x32_bf16 v[88:91], v[158:161], v[226:229], v[88:91]
	v_mfma_f32_16x16x32_bf16 v[92:95], v[162:165], v[226:229], v[92:95]
	v_mfma_f32_16x16x32_bf16 v[96:99], v[214:217], v[226:229], v[96:99]
	v_mfma_f32_16x16x32_bf16 v[36:39], v[218:221], v[226:229], v[36:39]
	ds_read_b128 v[226:229], v6 offset:15360
	s_waitcnt lgkmcnt(3)
	v_mfma_f32_16x16x32_bf16 v[104:107], v[158:161], v[166:169], v[104:107]
	v_mfma_f32_16x16x32_bf16 v[108:111], v[162:165], v[166:169], v[108:111]
	v_mfma_f32_16x16x32_bf16 v[112:115], v[214:217], v[166:169], v[112:115]
	v_mfma_f32_16x16x32_bf16 v[52:55], v[218:221], v[166:169], v[52:55]
	s_waitcnt lgkmcnt(2)
	v_mfma_f32_16x16x32_bf16 v[116:119], v[158:161], v[178:181], v[116:119]
	v_mfma_f32_16x16x32_bf16 v[120:123], v[162:165], v[178:181], v[120:123]
	v_mfma_f32_16x16x32_bf16 v[124:127], v[214:217], v[178:181], v[124:127]
	v_mfma_f32_16x16x32_bf16 v[68:71], v[218:221], v[178:181], v[68:71]
	s_waitcnt lgkmcnt(1)
	v_mfma_f32_16x16x32_bf16 v[128:131], v[158:161], v[222:225], v[128:131]
	v_mfma_f32_16x16x32_bf16 v[132:135], v[162:165], v[222:225], v[132:135]
	v_mfma_f32_16x16x32_bf16 v[136:139], v[214:217], v[222:225], v[136:139]
	v_mfma_f32_16x16x32_bf16 v[84:87], v[218:221], v[222:225], v[84:87]
	s_waitcnt lgkmcnt(0)
	v_mfma_f32_16x16x32_bf16 v[100:103], v[158:161], v[226:229], v[100:103]
	v_mfma_f32_16x16x32_bf16 v[140:143], v[162:165], v[226:229], v[140:143]
	v_mfma_f32_16x16x32_bf16 v[150:153], v[214:217], v[226:229], v[150:153]
	v_mfma_f32_16x16x32_bf16 v[154:157], v[218:221], v[226:229], v[154:157]
	s_add_u32 s46, s0, 0x1000
	s_addc_u32 s47, s1, 0
	s_add_u32 s48, s14, 0x1000
	s_waitcnt vmcnt(0)
	s_barrier
	s_addc_u32 s49, s15, 0
	ds_read_b128 v[158:161], v8
	ds_read_b128 v[162:165], v12
	ds_read_b128 v[166:169], v9
	ds_read_b128 v[178:181], v13
	ds_read_b128 v[214:217], v11
	ds_read_b128 v[218:221], v10
	ds_read_b128 v[222:225], v14
	ds_read_b128 v[226:229], v15
	s_waitcnt lgkmcnt(6)
	v_mfma_f32_16x16x32_bf16 v[40:43], v[158:161], v[162:165], v[40:43]
	s_waitcnt lgkmcnt(5)
	v_mfma_f32_16x16x32_bf16 v[44:47], v[166:169], v[162:165], v[44:47]
	s_waitcnt lgkmcnt(4)
	v_mfma_f32_16x16x32_bf16 v[56:59], v[158:161], v[178:181], v[56:59]
	s_mov_b32 m0, s27
	v_mfma_f32_16x16x32_bf16 v[60:63], v[166:169], v[178:181], v[60:63]
	global_load_lds_dwordx4 v0, s[46:47]
	s_waitcnt lgkmcnt(3)
	v_mfma_f32_16x16x32_bf16 v[48:51], v[214:217], v[162:165], v[48:51]
	v_mfma_f32_16x16x32_bf16 v[64:67], v[214:217], v[178:181], v[64:67]
	s_waitcnt lgkmcnt(2)
	v_mfma_f32_16x16x32_bf16 v[174:177], v[218:221], v[162:165], v[174:177]
	ds_read_b128 v[162:165], v16
	v_mfma_f32_16x16x32_bf16 v[170:173], v[218:221], v[178:181], v[170:173]
	ds_read_b128 v[178:181], v17
	s_waitcnt lgkmcnt(3)
	s_mov_b32 m0, s28
	v_mfma_f32_16x16x32_bf16 v[72:75], v[158:161], v[222:225], v[72:75]
	global_load_lds_dwordx4 v0, s[48:49]
	v_mfma_f32_16x16x32_bf16 v[76:79], v[166:169], v[222:225], v[76:79]
	v_mfma_f32_16x16x32_bf16 v[80:83], v[214:217], v[222:225], v[80:83]
	v_mfma_f32_16x16x32_bf16 v[32:35], v[218:221], v[222:225], v[32:35]
	ds_read_b128 v[222:225], v18
	s_waitcnt lgkmcnt(3)
	v_mfma_f32_16x16x32_bf16 v[88:91], v[158:161], v[226:229], v[88:91]
	s_mov_b32 m0, s29
	v_mfma_f32_16x16x32_bf16 v[92:95], v[166:169], v[226:229], v[92:95]
	global_load_lds_dwordx4 v2, s[46:47]
	v_mfma_f32_16x16x32_bf16 v[96:99], v[214:217], v[226:229], v[96:99]
	v_mfma_f32_16x16x32_bf16 v[36:39], v[218:221], v[226:229], v[36:39]
	ds_read_b128 v[226:229], v19
	s_waitcnt lgkmcnt(3)
	v_mfma_f32_16x16x32_bf16 v[104:107], v[158:161], v[162:165], v[104:107]
	s_waitcnt lgkmcnt(2)
	v_mfma_f32_16x16x32_bf16 v[116:119], v[158:161], v[178:181], v[116:119]
	s_waitcnt lgkmcnt(1)
	s_mov_b32 m0, s30
	v_mfma_f32_16x16x32_bf16 v[128:131], v[158:161], v[222:225], v[128:131]
	global_load_lds_dwordx4 v2, s[48:49]
	s_waitcnt lgkmcnt(0)
	v_mfma_f32_16x16x32_bf16 v[100:103], v[158:161], v[226:229], v[100:103]
	ds_read_b128 v[158:161], v20
	v_mfma_f32_16x16x32_bf16 v[108:111], v[166:169], v[162:165], v[108:111]
	v_mfma_f32_16x16x32_bf16 v[120:123], v[166:169], v[178:181], v[120:123]
	v_mfma_f32_16x16x32_bf16 v[132:135], v[166:169], v[222:225], v[132:135]
	s_mov_b32 m0, s31
	v_mfma_f32_16x16x32_bf16 v[140:143], v[166:169], v[226:229], v[140:143]
	global_load_lds_dwordx4 v4, s[46:47]
	ds_read_b128 v[166:169], v24
	v_mfma_f32_16x16x32_bf16 v[112:115], v[214:217], v[162:165], v[112:115]
	v_mfma_f32_16x16x32_bf16 v[52:55], v[218:221], v[162:165], v[52:55]
	ds_read_b128 v[162:165], v21
	v_mfma_f32_16x16x32_bf16 v[124:127], v[214:217], v[178:181], v[124:127]
	v_mfma_f32_16x16x32_bf16 v[68:71], v[218:221], v[178:181], v[68:71]
	ds_read_b128 v[178:181], v25
	s_mov_b32 m0, s34
	v_mfma_f32_16x16x32_bf16 v[136:139], v[214:217], v[222:225], v[136:139]
	global_load_lds_dwordx4 v4, s[48:49]
	v_mfma_f32_16x16x32_bf16 v[84:87], v[218:221], v[222:225], v[84:87]
	ds_read_b128 v[222:225], v26
	v_mfma_f32_16x16x32_bf16 v[150:153], v[214:217], v[226:229], v[150:153]
	ds_read_b128 v[214:217], v23
	v_mfma_f32_16x16x32_bf16 v[154:157], v[218:221], v[226:229], v[154:157]
	ds_read_b128 v[218:221], v22
	ds_read_b128 v[226:229], v27
	s_waitcnt lgkmcnt(6)
	v_mfma_f32_16x16x32_bf16 v[40:43], v[158:161], v[166:169], v[40:43]
	s_waitcnt lgkmcnt(5)
	s_mov_b32 m0, s35
	v_mfma_f32_16x16x32_bf16 v[44:47], v[162:165], v[166:169], v[44:47]
	global_load_lds_dwordx4 v146, s[46:47]
	s_waitcnt lgkmcnt(4)
	v_mfma_f32_16x16x32_bf16 v[56:59], v[158:161], v[178:181], v[56:59]
	v_mfma_f32_16x16x32_bf16 v[60:63], v[162:165], v[178:181], v[60:63]
	s_waitcnt lgkmcnt(3)
	v_mfma_f32_16x16x32_bf16 v[72:75], v[158:161], v[222:225], v[72:75]
	v_mfma_f32_16x16x32_bf16 v[76:79], v[162:165], v[222:225], v[76:79]
	s_waitcnt lgkmcnt(2)
	s_mov_b32 m0, s36
	v_mfma_f32_16x16x32_bf16 v[48:51], v[214:217], v[166:169], v[48:51]
	global_load_lds_dwordx4 v146, s[48:49]
	s_waitcnt lgkmcnt(1)
	v_mfma_f32_16x16x32_bf16 v[174:177], v[218:221], v[166:169], v[174:177]
	ds_read_b128 v[166:169], v28
	v_mfma_f32_16x16x32_bf16 v[64:67], v[214:217], v[178:181], v[64:67]
	v_mfma_f32_16x16x32_bf16 v[170:173], v[218:221], v[178:181], v[170:173]
	ds_read_b128 v[178:181], v29
	v_mfma_f32_16x16x32_bf16 v[80:83], v[214:217], v[222:225], v[80:83]
	v_mfma_f32_16x16x32_bf16 v[32:35], v[218:221], v[222:225], v[32:35]
	ds_read_b128 v[222:225], v30
	s_waitcnt lgkmcnt(3)
	v_mfma_f32_16x16x32_bf16 v[88:91], v[158:161], v[226:229], v[88:91]
	v_mfma_f32_16x16x32_bf16 v[92:95], v[162:165], v[226:229], v[92:95]
	v_mfma_f32_16x16x32_bf16 v[96:99], v[214:217], v[226:229], v[96:99]
	v_mfma_f32_16x16x32_bf16 v[36:39], v[218:221], v[226:229], v[36:39]
	ds_read_b128 v[226:229], v31
	s_waitcnt lgkmcnt(3)
	v_mfma_f32_16x16x32_bf16 v[104:107], v[158:161], v[166:169], v[104:107]
	v_mfma_f32_16x16x32_bf16 v[108:111], v[162:165], v[166:169], v[108:111]
	v_mfma_f32_16x16x32_bf16 v[112:115], v[214:217], v[166:169], v[112:115]
	v_mfma_f32_16x16x32_bf16 v[52:55], v[218:221], v[166:169], v[52:55]
	s_waitcnt lgkmcnt(2)
	v_mfma_f32_16x16x32_bf16 v[116:119], v[158:161], v[178:181], v[116:119]
	v_mfma_f32_16x16x32_bf16 v[120:123], v[162:165], v[178:181], v[120:123]
	v_mfma_f32_16x16x32_bf16 v[124:127], v[214:217], v[178:181], v[124:127]
	v_mfma_f32_16x16x32_bf16 v[68:71], v[218:221], v[178:181], v[68:71]
	s_waitcnt lgkmcnt(1)
	v_mfma_f32_16x16x32_bf16 v[128:131], v[158:161], v[222:225], v[128:131]
	v_mfma_f32_16x16x32_bf16 v[132:135], v[162:165], v[222:225], v[132:135]
	v_mfma_f32_16x16x32_bf16 v[136:139], v[214:217], v[222:225], v[136:139]
	v_mfma_f32_16x16x32_bf16 v[84:87], v[218:221], v[222:225], v[84:87]
	s_waitcnt lgkmcnt(0)
	v_mfma_f32_16x16x32_bf16 v[100:103], v[158:161], v[226:229], v[100:103]
	v_mfma_f32_16x16x32_bf16 v[140:143], v[162:165], v[226:229], v[140:143]
	v_mfma_f32_16x16x32_bf16 v[150:153], v[214:217], v[226:229], v[150:153]
	v_mfma_f32_16x16x32_bf16 v[154:157], v[218:221], v[226:229], v[154:157]
	s_add_u32 s46, s0, 0x1080
	s_addc_u32 s47, s1, 0
	s_add_u32 s48, s14, 0x1080
	s_waitcnt vmcnt(0)
	s_barrier
	s_addc_u32 s49, s15, 0
	ds_read_b128 v[158:161], v7 offset:32768
	ds_read_b128 v[162:165], v6
	ds_read_b128 v[166:169], v7 offset:34816
	ds_read_b128 v[178:181], v6 offset:2048
	ds_read_b128 v[214:217], v7 offset:36864
	ds_read_b128 v[218:221], v7 offset:38912
	ds_read_b128 v[222:225], v6 offset:4096
	ds_read_b128 v[226:229], v6 offset:6144
	s_waitcnt lgkmcnt(6)
	v_mfma_f32_16x16x32_bf16 v[40:43], v[158:161], v[162:165], v[40:43]
	s_waitcnt lgkmcnt(5)
	v_mfma_f32_16x16x32_bf16 v[44:47], v[166:169], v[162:165], v[44:47]
	s_waitcnt lgkmcnt(4)
	v_mfma_f32_16x16x32_bf16 v[56:59], v[158:161], v[178:181], v[56:59]
	s_mov_b32 m0, s38
	v_mfma_f32_16x16x32_bf16 v[60:63], v[166:169], v[178:181], v[60:63]
	global_load_lds_dwordx4 v0, s[46:47]
	s_waitcnt lgkmcnt(3)
	v_mfma_f32_16x16x32_bf16 v[48:51], v[214:217], v[162:165], v[48:51]
	v_mfma_f32_16x16x32_bf16 v[64:67], v[214:217], v[178:181], v[64:67]
	s_waitcnt lgkmcnt(2)
	v_mfma_f32_16x16x32_bf16 v[174:177], v[218:221], v[162:165], v[174:177]
	ds_read_b128 v[162:165], v6 offset:8192
	v_mfma_f32_16x16x32_bf16 v[170:173], v[218:221], v[178:181], v[170:173]
	ds_read_b128 v[178:181], v6 offset:10240
	s_waitcnt lgkmcnt(3)
	s_mov_b32 m0, s37
	v_mfma_f32_16x16x32_bf16 v[72:75], v[158:161], v[222:225], v[72:75]
	global_load_lds_dwordx4 v0, s[48:49]
	v_mfma_f32_16x16x32_bf16 v[76:79], v[166:169], v[222:225], v[76:79]
	v_mfma_f32_16x16x32_bf16 v[80:83], v[214:217], v[222:225], v[80:83]
	v_mfma_f32_16x16x32_bf16 v[32:35], v[218:221], v[222:225], v[32:35]
	ds_read_b128 v[222:225], v6 offset:12288
	s_waitcnt lgkmcnt(3)
	v_mfma_f32_16x16x32_bf16 v[88:91], v[158:161], v[226:229], v[88:91]
	s_mov_b32 m0, s39
	v_mfma_f32_16x16x32_bf16 v[92:95], v[166:169], v[226:229], v[92:95]
	global_load_lds_dwordx4 v2, s[46:47]
	v_mfma_f32_16x16x32_bf16 v[96:99], v[214:217], v[226:229], v[96:99]
	v_mfma_f32_16x16x32_bf16 v[36:39], v[218:221], v[226:229], v[36:39]
	ds_read_b128 v[226:229], v6 offset:14336
	s_waitcnt lgkmcnt(3)
	v_mfma_f32_16x16x32_bf16 v[104:107], v[158:161], v[162:165], v[104:107]
	s_waitcnt lgkmcnt(2)
	v_mfma_f32_16x16x32_bf16 v[116:119], v[158:161], v[178:181], v[116:119]
	s_waitcnt lgkmcnt(1)
	s_mov_b32 m0, s40
	v_mfma_f32_16x16x32_bf16 v[128:131], v[158:161], v[222:225], v[128:131]
	global_load_lds_dwordx4 v2, s[48:49]
	s_waitcnt lgkmcnt(0)
	v_mfma_f32_16x16x32_bf16 v[100:103], v[158:161], v[226:229], v[100:103]
	ds_read_b128 v[158:161], v7 offset:33792
	v_mfma_f32_16x16x32_bf16 v[108:111], v[166:169], v[162:165], v[108:111]
	v_mfma_f32_16x16x32_bf16 v[120:123], v[166:169], v[178:181], v[120:123]
	v_mfma_f32_16x16x32_bf16 v[132:135], v[166:169], v[222:225], v[132:135]
	s_mov_b32 m0, s41
	v_mfma_f32_16x16x32_bf16 v[140:143], v[166:169], v[226:229], v[140:143]
	global_load_lds_dwordx4 v4, s[46:47]
	ds_read_b128 v[166:169], v6 offset:1024
	v_mfma_f32_16x16x32_bf16 v[112:115], v[214:217], v[162:165], v[112:115]
	v_mfma_f32_16x16x32_bf16 v[52:55], v[218:221], v[162:165], v[52:55]
	ds_read_b128 v[162:165], v7 offset:35840
	v_mfma_f32_16x16x32_bf16 v[124:127], v[214:217], v[178:181], v[124:127]
	v_mfma_f32_16x16x32_bf16 v[68:71], v[218:221], v[178:181], v[68:71]
	ds_read_b128 v[178:181], v6 offset:3072
	s_mov_b32 m0, s42
	v_mfma_f32_16x16x32_bf16 v[136:139], v[214:217], v[222:225], v[136:139]
	global_load_lds_dwordx4 v4, s[48:49]
	v_mfma_f32_16x16x32_bf16 v[84:87], v[218:221], v[222:225], v[84:87]
	ds_read_b128 v[222:225], v6 offset:5120
	v_mfma_f32_16x16x32_bf16 v[150:153], v[214:217], v[226:229], v[150:153]
	ds_read_b128 v[214:217], v7 offset:37888
	v_mfma_f32_16x16x32_bf16 v[154:157], v[218:221], v[226:229], v[154:157]
	ds_read_b128 v[218:221], v7 offset:39936
	ds_read_b128 v[226:229], v6 offset:7168
	s_waitcnt lgkmcnt(6)
	v_mfma_f32_16x16x32_bf16 v[40:43], v[158:161], v[166:169], v[40:43]
	s_waitcnt lgkmcnt(5)
	s_mov_b32 m0, s43
	v_mfma_f32_16x16x32_bf16 v[44:47], v[162:165], v[166:169], v[44:47]
	global_load_lds_dwordx4 v146, s[46:47]
	s_waitcnt lgkmcnt(4)
	v_mfma_f32_16x16x32_bf16 v[56:59], v[158:161], v[178:181], v[56:59]
	v_mfma_f32_16x16x32_bf16 v[60:63], v[162:165], v[178:181], v[60:63]
	s_waitcnt lgkmcnt(3)
	v_mfma_f32_16x16x32_bf16 v[72:75], v[158:161], v[222:225], v[72:75]
	v_mfma_f32_16x16x32_bf16 v[76:79], v[162:165], v[222:225], v[76:79]
	s_waitcnt lgkmcnt(2)
	s_mov_b32 m0, s44
	v_mfma_f32_16x16x32_bf16 v[48:51], v[214:217], v[166:169], v[48:51]
	global_load_lds_dwordx4 v146, s[48:49]
	s_waitcnt lgkmcnt(1)
	v_mfma_f32_16x16x32_bf16 v[174:177], v[218:221], v[166:169], v[174:177]
	ds_read_b128 v[166:169], v6 offset:9216
	v_mfma_f32_16x16x32_bf16 v[64:67], v[214:217], v[178:181], v[64:67]
	v_mfma_f32_16x16x32_bf16 v[170:173], v[218:221], v[178:181], v[170:173]
	ds_read_b128 v[178:181], v6 offset:11264
	v_mfma_f32_16x16x32_bf16 v[80:83], v[214:217], v[222:225], v[80:83]
	v_mfma_f32_16x16x32_bf16 v[32:35], v[218:221], v[222:225], v[32:35]
	ds_read_b128 v[222:225], v6 offset:13312
	s_waitcnt lgkmcnt(3)
	v_mfma_f32_16x16x32_bf16 v[88:91], v[158:161], v[226:229], v[88:91]
	v_mfma_f32_16x16x32_bf16 v[92:95], v[162:165], v[226:229], v[92:95]
	v_mfma_f32_16x16x32_bf16 v[96:99], v[214:217], v[226:229], v[96:99]
	v_mfma_f32_16x16x32_bf16 v[36:39], v[218:221], v[226:229], v[36:39]
	ds_read_b128 v[226:229], v6 offset:15360
	s_waitcnt lgkmcnt(3)
	v_mfma_f32_16x16x32_bf16 v[104:107], v[158:161], v[166:169], v[104:107]
	v_mfma_f32_16x16x32_bf16 v[108:111], v[162:165], v[166:169], v[108:111]
	v_mfma_f32_16x16x32_bf16 v[112:115], v[214:217], v[166:169], v[112:115]
	v_mfma_f32_16x16x32_bf16 v[52:55], v[218:221], v[166:169], v[52:55]
	s_waitcnt lgkmcnt(2)
	v_mfma_f32_16x16x32_bf16 v[116:119], v[158:161], v[178:181], v[116:119]
	v_mfma_f32_16x16x32_bf16 v[120:123], v[162:165], v[178:181], v[120:123]
	v_mfma_f32_16x16x32_bf16 v[124:127], v[214:217], v[178:181], v[124:127]
	v_mfma_f32_16x16x32_bf16 v[68:71], v[218:221], v[178:181], v[68:71]
	s_waitcnt lgkmcnt(1)
	v_mfma_f32_16x16x32_bf16 v[128:131], v[158:161], v[222:225], v[128:131]
	v_mfma_f32_16x16x32_bf16 v[132:135], v[162:165], v[222:225], v[132:135]
	v_mfma_f32_16x16x32_bf16 v[136:139], v[214:217], v[222:225], v[136:139]
	v_mfma_f32_16x16x32_bf16 v[84:87], v[218:221], v[222:225], v[84:87]
	s_waitcnt lgkmcnt(0)
	v_mfma_f32_16x16x32_bf16 v[100:103], v[158:161], v[226:229], v[100:103]
	v_mfma_f32_16x16x32_bf16 v[140:143], v[162:165], v[226:229], v[140:143]
	v_mfma_f32_16x16x32_bf16 v[150:153], v[214:217], v[226:229], v[150:153]
	v_mfma_f32_16x16x32_bf16 v[154:157], v[218:221], v[226:229], v[154:157]
	s_add_u32 s46, s0, 0x1100
	s_addc_u32 s47, s1, 0
	s_add_u32 s48, s14, 0x1100
	s_waitcnt vmcnt(0)
	s_barrier
	s_addc_u32 s49, s15, 0
	ds_read_b128 v[158:161], v8
	ds_read_b128 v[162:165], v12
	ds_read_b128 v[166:169], v9
	ds_read_b128 v[178:181], v13
	ds_read_b128 v[214:217], v11
	ds_read_b128 v[218:221], v10
	ds_read_b128 v[222:225], v14
	ds_read_b128 v[226:229], v15
	s_waitcnt lgkmcnt(6)
	v_mfma_f32_16x16x32_bf16 v[40:43], v[158:161], v[162:165], v[40:43]
	s_waitcnt lgkmcnt(5)
	v_mfma_f32_16x16x32_bf16 v[44:47], v[166:169], v[162:165], v[44:47]
	s_waitcnt lgkmcnt(4)
	v_mfma_f32_16x16x32_bf16 v[56:59], v[158:161], v[178:181], v[56:59]
	s_mov_b32 m0, s27
	v_mfma_f32_16x16x32_bf16 v[60:63], v[166:169], v[178:181], v[60:63]
	global_load_lds_dwordx4 v0, s[46:47]
	s_waitcnt lgkmcnt(3)
	v_mfma_f32_16x16x32_bf16 v[48:51], v[214:217], v[162:165], v[48:51]
	v_mfma_f32_16x16x32_bf16 v[64:67], v[214:217], v[178:181], v[64:67]
	s_waitcnt lgkmcnt(2)
	v_mfma_f32_16x16x32_bf16 v[174:177], v[218:221], v[162:165], v[174:177]
	ds_read_b128 v[162:165], v16
	v_mfma_f32_16x16x32_bf16 v[170:173], v[218:221], v[178:181], v[170:173]
	ds_read_b128 v[178:181], v17
	s_waitcnt lgkmcnt(3)
	s_mov_b32 m0, s28
	v_mfma_f32_16x16x32_bf16 v[72:75], v[158:161], v[222:225], v[72:75]
	global_load_lds_dwordx4 v0, s[48:49]
	v_mfma_f32_16x16x32_bf16 v[76:79], v[166:169], v[222:225], v[76:79]
	v_mfma_f32_16x16x32_bf16 v[80:83], v[214:217], v[222:225], v[80:83]
	v_mfma_f32_16x16x32_bf16 v[32:35], v[218:221], v[222:225], v[32:35]
	ds_read_b128 v[222:225], v18
	s_waitcnt lgkmcnt(3)
	v_mfma_f32_16x16x32_bf16 v[88:91], v[158:161], v[226:229], v[88:91]
	s_mov_b32 m0, s29
	v_mfma_f32_16x16x32_bf16 v[92:95], v[166:169], v[226:229], v[92:95]
	global_load_lds_dwordx4 v2, s[46:47]
	v_mfma_f32_16x16x32_bf16 v[96:99], v[214:217], v[226:229], v[96:99]
	v_mfma_f32_16x16x32_bf16 v[36:39], v[218:221], v[226:229], v[36:39]
	ds_read_b128 v[226:229], v19
	s_waitcnt lgkmcnt(3)
	v_mfma_f32_16x16x32_bf16 v[104:107], v[158:161], v[162:165], v[104:107]
	s_waitcnt lgkmcnt(2)
	v_mfma_f32_16x16x32_bf16 v[116:119], v[158:161], v[178:181], v[116:119]
	s_waitcnt lgkmcnt(1)
	s_mov_b32 m0, s30
	v_mfma_f32_16x16x32_bf16 v[128:131], v[158:161], v[222:225], v[128:131]
	global_load_lds_dwordx4 v2, s[48:49]
	s_waitcnt lgkmcnt(0)
	v_mfma_f32_16x16x32_bf16 v[100:103], v[158:161], v[226:229], v[100:103]
	ds_read_b128 v[158:161], v20
	v_mfma_f32_16x16x32_bf16 v[108:111], v[166:169], v[162:165], v[108:111]
	v_mfma_f32_16x16x32_bf16 v[120:123], v[166:169], v[178:181], v[120:123]
	v_mfma_f32_16x16x32_bf16 v[132:135], v[166:169], v[222:225], v[132:135]
	s_mov_b32 m0, s31
	v_mfma_f32_16x16x32_bf16 v[140:143], v[166:169], v[226:229], v[140:143]
	global_load_lds_dwordx4 v4, s[46:47]
	ds_read_b128 v[166:169], v24
	v_mfma_f32_16x16x32_bf16 v[112:115], v[214:217], v[162:165], v[112:115]
	v_mfma_f32_16x16x32_bf16 v[52:55], v[218:221], v[162:165], v[52:55]
	ds_read_b128 v[162:165], v21
	v_mfma_f32_16x16x32_bf16 v[124:127], v[214:217], v[178:181], v[124:127]
	v_mfma_f32_16x16x32_bf16 v[68:71], v[218:221], v[178:181], v[68:71]
	ds_read_b128 v[178:181], v25
	s_mov_b32 m0, s34
	v_mfma_f32_16x16x32_bf16 v[136:139], v[214:217], v[222:225], v[136:139]
	global_load_lds_dwordx4 v4, s[48:49]
	v_mfma_f32_16x16x32_bf16 v[84:87], v[218:221], v[222:225], v[84:87]
	ds_read_b128 v[222:225], v26
	v_mfma_f32_16x16x32_bf16 v[150:153], v[214:217], v[226:229], v[150:153]
	ds_read_b128 v[214:217], v23
	v_mfma_f32_16x16x32_bf16 v[154:157], v[218:221], v[226:229], v[154:157]
	ds_read_b128 v[218:221], v22
	ds_read_b128 v[226:229], v27
	s_waitcnt lgkmcnt(6)
	v_mfma_f32_16x16x32_bf16 v[40:43], v[158:161], v[166:169], v[40:43]
	s_waitcnt lgkmcnt(5)
	s_mov_b32 m0, s35
	v_mfma_f32_16x16x32_bf16 v[44:47], v[162:165], v[166:169], v[44:47]
	global_load_lds_dwordx4 v146, s[46:47]
	s_waitcnt lgkmcnt(4)
	v_mfma_f32_16x16x32_bf16 v[56:59], v[158:161], v[178:181], v[56:59]
	v_mfma_f32_16x16x32_bf16 v[60:63], v[162:165], v[178:181], v[60:63]
	s_waitcnt lgkmcnt(3)
	v_mfma_f32_16x16x32_bf16 v[72:75], v[158:161], v[222:225], v[72:75]
	v_mfma_f32_16x16x32_bf16 v[76:79], v[162:165], v[222:225], v[76:79]
	s_waitcnt lgkmcnt(2)
	s_mov_b32 m0, s36
	v_mfma_f32_16x16x32_bf16 v[48:51], v[214:217], v[166:169], v[48:51]
	global_load_lds_dwordx4 v146, s[48:49]
	s_waitcnt lgkmcnt(1)
	v_mfma_f32_16x16x32_bf16 v[174:177], v[218:221], v[166:169], v[174:177]
	ds_read_b128 v[166:169], v28
	v_mfma_f32_16x16x32_bf16 v[64:67], v[214:217], v[178:181], v[64:67]
	v_mfma_f32_16x16x32_bf16 v[170:173], v[218:221], v[178:181], v[170:173]
	ds_read_b128 v[178:181], v29
	v_mfma_f32_16x16x32_bf16 v[80:83], v[214:217], v[222:225], v[80:83]
	v_mfma_f32_16x16x32_bf16 v[32:35], v[218:221], v[222:225], v[32:35]
	ds_read_b128 v[222:225], v30
	s_waitcnt lgkmcnt(3)
	v_mfma_f32_16x16x32_bf16 v[88:91], v[158:161], v[226:229], v[88:91]
	v_mfma_f32_16x16x32_bf16 v[92:95], v[162:165], v[226:229], v[92:95]
	v_mfma_f32_16x16x32_bf16 v[96:99], v[214:217], v[226:229], v[96:99]
	v_mfma_f32_16x16x32_bf16 v[36:39], v[218:221], v[226:229], v[36:39]
	ds_read_b128 v[226:229], v31
	s_waitcnt lgkmcnt(3)
	v_mfma_f32_16x16x32_bf16 v[104:107], v[158:161], v[166:169], v[104:107]
	v_mfma_f32_16x16x32_bf16 v[108:111], v[162:165], v[166:169], v[108:111]
	v_mfma_f32_16x16x32_bf16 v[112:115], v[214:217], v[166:169], v[112:115]
	v_mfma_f32_16x16x32_bf16 v[52:55], v[218:221], v[166:169], v[52:55]
	s_waitcnt lgkmcnt(2)
	v_mfma_f32_16x16x32_bf16 v[116:119], v[158:161], v[178:181], v[116:119]
	v_mfma_f32_16x16x32_bf16 v[120:123], v[162:165], v[178:181], v[120:123]
	v_mfma_f32_16x16x32_bf16 v[124:127], v[214:217], v[178:181], v[124:127]
	v_mfma_f32_16x16x32_bf16 v[68:71], v[218:221], v[178:181], v[68:71]
	s_waitcnt lgkmcnt(1)
	v_mfma_f32_16x16x32_bf16 v[128:131], v[158:161], v[222:225], v[128:131]
	v_mfma_f32_16x16x32_bf16 v[132:135], v[162:165], v[222:225], v[132:135]
	v_mfma_f32_16x16x32_bf16 v[136:139], v[214:217], v[222:225], v[136:139]
	v_mfma_f32_16x16x32_bf16 v[84:87], v[218:221], v[222:225], v[84:87]
	s_waitcnt lgkmcnt(0)
	v_mfma_f32_16x16x32_bf16 v[100:103], v[158:161], v[226:229], v[100:103]
	v_mfma_f32_16x16x32_bf16 v[140:143], v[162:165], v[226:229], v[140:143]
	v_mfma_f32_16x16x32_bf16 v[150:153], v[214:217], v[226:229], v[150:153]
	v_mfma_f32_16x16x32_bf16 v[154:157], v[218:221], v[226:229], v[154:157]
	s_add_u32 s46, s0, 0x1180
	s_addc_u32 s47, s1, 0
	s_add_u32 s48, s14, 0x1180
	s_waitcnt vmcnt(0)
	s_barrier
	s_addc_u32 s49, s15, 0
	ds_read_b128 v[158:161], v7 offset:32768
	ds_read_b128 v[162:165], v6
	ds_read_b128 v[166:169], v7 offset:34816
	ds_read_b128 v[178:181], v6 offset:2048
	ds_read_b128 v[214:217], v7 offset:36864
	ds_read_b128 v[218:221], v7 offset:38912
	ds_read_b128 v[222:225], v6 offset:4096
	ds_read_b128 v[226:229], v6 offset:6144
	s_waitcnt lgkmcnt(6)
	v_mfma_f32_16x16x32_bf16 v[40:43], v[158:161], v[162:165], v[40:43]
	s_waitcnt lgkmcnt(5)
	v_mfma_f32_16x16x32_bf16 v[44:47], v[166:169], v[162:165], v[44:47]
	s_waitcnt lgkmcnt(4)
	v_mfma_f32_16x16x32_bf16 v[56:59], v[158:161], v[178:181], v[56:59]
	s_mov_b32 m0, s38
	v_mfma_f32_16x16x32_bf16 v[60:63], v[166:169], v[178:181], v[60:63]
	global_load_lds_dwordx4 v0, s[46:47]
	s_waitcnt lgkmcnt(3)
	v_mfma_f32_16x16x32_bf16 v[48:51], v[214:217], v[162:165], v[48:51]
	v_mfma_f32_16x16x32_bf16 v[64:67], v[214:217], v[178:181], v[64:67]
	s_waitcnt lgkmcnt(2)
	v_mfma_f32_16x16x32_bf16 v[174:177], v[218:221], v[162:165], v[174:177]
	ds_read_b128 v[162:165], v6 offset:8192
	v_mfma_f32_16x16x32_bf16 v[170:173], v[218:221], v[178:181], v[170:173]
	ds_read_b128 v[178:181], v6 offset:10240
	s_waitcnt lgkmcnt(3)
	s_mov_b32 m0, s37
	v_mfma_f32_16x16x32_bf16 v[72:75], v[158:161], v[222:225], v[72:75]
	global_load_lds_dwordx4 v0, s[48:49]
	v_mfma_f32_16x16x32_bf16 v[76:79], v[166:169], v[222:225], v[76:79]
	v_mfma_f32_16x16x32_bf16 v[80:83], v[214:217], v[222:225], v[80:83]
	v_mfma_f32_16x16x32_bf16 v[32:35], v[218:221], v[222:225], v[32:35]
	ds_read_b128 v[222:225], v6 offset:12288
	s_waitcnt lgkmcnt(3)
	v_mfma_f32_16x16x32_bf16 v[88:91], v[158:161], v[226:229], v[88:91]
	s_mov_b32 m0, s39
	v_mfma_f32_16x16x32_bf16 v[92:95], v[166:169], v[226:229], v[92:95]
	global_load_lds_dwordx4 v2, s[46:47]
	v_mfma_f32_16x16x32_bf16 v[96:99], v[214:217], v[226:229], v[96:99]
	v_mfma_f32_16x16x32_bf16 v[36:39], v[218:221], v[226:229], v[36:39]
	ds_read_b128 v[226:229], v6 offset:14336
	s_waitcnt lgkmcnt(3)
	v_mfma_f32_16x16x32_bf16 v[104:107], v[158:161], v[162:165], v[104:107]
	s_waitcnt lgkmcnt(2)
	v_mfma_f32_16x16x32_bf16 v[116:119], v[158:161], v[178:181], v[116:119]
	s_waitcnt lgkmcnt(1)
	s_mov_b32 m0, s40
	v_mfma_f32_16x16x32_bf16 v[128:131], v[158:161], v[222:225], v[128:131]
	global_load_lds_dwordx4 v2, s[48:49]
	s_waitcnt lgkmcnt(0)
	v_mfma_f32_16x16x32_bf16 v[100:103], v[158:161], v[226:229], v[100:103]
	ds_read_b128 v[158:161], v7 offset:33792
	v_mfma_f32_16x16x32_bf16 v[108:111], v[166:169], v[162:165], v[108:111]
	v_mfma_f32_16x16x32_bf16 v[120:123], v[166:169], v[178:181], v[120:123]
	v_mfma_f32_16x16x32_bf16 v[132:135], v[166:169], v[222:225], v[132:135]
	s_mov_b32 m0, s41
	v_mfma_f32_16x16x32_bf16 v[140:143], v[166:169], v[226:229], v[140:143]
	global_load_lds_dwordx4 v4, s[46:47]
	ds_read_b128 v[166:169], v6 offset:1024
	v_mfma_f32_16x16x32_bf16 v[112:115], v[214:217], v[162:165], v[112:115]
	v_mfma_f32_16x16x32_bf16 v[52:55], v[218:221], v[162:165], v[52:55]
	ds_read_b128 v[162:165], v7 offset:35840
	v_mfma_f32_16x16x32_bf16 v[124:127], v[214:217], v[178:181], v[124:127]
	v_mfma_f32_16x16x32_bf16 v[68:71], v[218:221], v[178:181], v[68:71]
	ds_read_b128 v[178:181], v6 offset:3072
	s_mov_b32 m0, s42
	v_mfma_f32_16x16x32_bf16 v[136:139], v[214:217], v[222:225], v[136:139]
	global_load_lds_dwordx4 v4, s[48:49]
	v_mfma_f32_16x16x32_bf16 v[84:87], v[218:221], v[222:225], v[84:87]
	ds_read_b128 v[222:225], v6 offset:5120
	v_mfma_f32_16x16x32_bf16 v[150:153], v[214:217], v[226:229], v[150:153]
	ds_read_b128 v[214:217], v7 offset:37888
	v_mfma_f32_16x16x32_bf16 v[154:157], v[218:221], v[226:229], v[154:157]
	ds_read_b128 v[218:221], v7 offset:39936
	ds_read_b128 v[226:229], v6 offset:7168
	s_waitcnt lgkmcnt(6)
	v_mfma_f32_16x16x32_bf16 v[40:43], v[158:161], v[166:169], v[40:43]
	s_waitcnt lgkmcnt(5)
	s_mov_b32 m0, s43
	v_mfma_f32_16x16x32_bf16 v[44:47], v[162:165], v[166:169], v[44:47]
	global_load_lds_dwordx4 v146, s[46:47]
	s_waitcnt lgkmcnt(4)
	v_mfma_f32_16x16x32_bf16 v[56:59], v[158:161], v[178:181], v[56:59]
	v_mfma_f32_16x16x32_bf16 v[60:63], v[162:165], v[178:181], v[60:63]
	s_waitcnt lgkmcnt(3)
	v_mfma_f32_16x16x32_bf16 v[72:75], v[158:161], v[222:225], v[72:75]
	v_mfma_f32_16x16x32_bf16 v[76:79], v[162:165], v[222:225], v[76:79]
	s_waitcnt lgkmcnt(2)
	s_mov_b32 m0, s44
	v_mfma_f32_16x16x32_bf16 v[48:51], v[214:217], v[166:169], v[48:51]
	global_load_lds_dwordx4 v146, s[48:49]
	s_waitcnt lgkmcnt(1)
	v_mfma_f32_16x16x32_bf16 v[174:177], v[218:221], v[166:169], v[174:177]
	ds_read_b128 v[166:169], v6 offset:9216
	v_mfma_f32_16x16x32_bf16 v[64:67], v[214:217], v[178:181], v[64:67]
	v_mfma_f32_16x16x32_bf16 v[170:173], v[218:221], v[178:181], v[170:173]
	ds_read_b128 v[178:181], v6 offset:11264
	v_mfma_f32_16x16x32_bf16 v[80:83], v[214:217], v[222:225], v[80:83]
	v_mfma_f32_16x16x32_bf16 v[32:35], v[218:221], v[222:225], v[32:35]
	ds_read_b128 v[222:225], v6 offset:13312
	s_waitcnt lgkmcnt(3)
	v_mfma_f32_16x16x32_bf16 v[88:91], v[158:161], v[226:229], v[88:91]
	v_mfma_f32_16x16x32_bf16 v[92:95], v[162:165], v[226:229], v[92:95]
	v_mfma_f32_16x16x32_bf16 v[96:99], v[214:217], v[226:229], v[96:99]
	v_mfma_f32_16x16x32_bf16 v[36:39], v[218:221], v[226:229], v[36:39]
	ds_read_b128 v[226:229], v6 offset:15360
	s_waitcnt lgkmcnt(3)
	v_mfma_f32_16x16x32_bf16 v[104:107], v[158:161], v[166:169], v[104:107]
	v_mfma_f32_16x16x32_bf16 v[108:111], v[162:165], v[166:169], v[108:111]
	v_mfma_f32_16x16x32_bf16 v[112:115], v[214:217], v[166:169], v[112:115]
	v_mfma_f32_16x16x32_bf16 v[52:55], v[218:221], v[166:169], v[52:55]
	s_waitcnt lgkmcnt(2)
	v_mfma_f32_16x16x32_bf16 v[116:119], v[158:161], v[178:181], v[116:119]
	v_mfma_f32_16x16x32_bf16 v[120:123], v[162:165], v[178:181], v[120:123]
	v_mfma_f32_16x16x32_bf16 v[124:127], v[214:217], v[178:181], v[124:127]
	v_mfma_f32_16x16x32_bf16 v[68:71], v[218:221], v[178:181], v[68:71]
	s_waitcnt lgkmcnt(1)
	v_mfma_f32_16x16x32_bf16 v[128:131], v[158:161], v[222:225], v[128:131]
	v_mfma_f32_16x16x32_bf16 v[132:135], v[162:165], v[222:225], v[132:135]
	v_mfma_f32_16x16x32_bf16 v[136:139], v[214:217], v[222:225], v[136:139]
	v_mfma_f32_16x16x32_bf16 v[84:87], v[218:221], v[222:225], v[84:87]
	s_waitcnt lgkmcnt(0)
	v_mfma_f32_16x16x32_bf16 v[100:103], v[158:161], v[226:229], v[100:103]
	v_mfma_f32_16x16x32_bf16 v[140:143], v[162:165], v[226:229], v[140:143]
	v_mfma_f32_16x16x32_bf16 v[150:153], v[214:217], v[226:229], v[150:153]
	v_mfma_f32_16x16x32_bf16 v[154:157], v[218:221], v[226:229], v[154:157]
	s_add_u32 s46, s0, 0x1200
	s_addc_u32 s47, s1, 0
	s_add_u32 s48, s14, 0x1200
	s_waitcnt vmcnt(0)
	s_barrier
	s_addc_u32 s49, s15, 0
	ds_read_b128 v[158:161], v8
	ds_read_b128 v[162:165], v12
	ds_read_b128 v[166:169], v9
	ds_read_b128 v[178:181], v13
	ds_read_b128 v[214:217], v11
	ds_read_b128 v[218:221], v10
	ds_read_b128 v[222:225], v14
	ds_read_b128 v[226:229], v15
	s_waitcnt lgkmcnt(6)
	v_mfma_f32_16x16x32_bf16 v[40:43], v[158:161], v[162:165], v[40:43]
	s_waitcnt lgkmcnt(5)
	v_mfma_f32_16x16x32_bf16 v[44:47], v[166:169], v[162:165], v[44:47]
	s_waitcnt lgkmcnt(4)
	v_mfma_f32_16x16x32_bf16 v[56:59], v[158:161], v[178:181], v[56:59]
	s_mov_b32 m0, s27
	v_mfma_f32_16x16x32_bf16 v[60:63], v[166:169], v[178:181], v[60:63]
	global_load_lds_dwordx4 v0, s[46:47]
	s_waitcnt lgkmcnt(3)
	v_mfma_f32_16x16x32_bf16 v[48:51], v[214:217], v[162:165], v[48:51]
	v_mfma_f32_16x16x32_bf16 v[64:67], v[214:217], v[178:181], v[64:67]
	s_waitcnt lgkmcnt(2)
	v_mfma_f32_16x16x32_bf16 v[174:177], v[218:221], v[162:165], v[174:177]
	ds_read_b128 v[162:165], v16
	v_mfma_f32_16x16x32_bf16 v[170:173], v[218:221], v[178:181], v[170:173]
	ds_read_b128 v[178:181], v17
	s_waitcnt lgkmcnt(3)
	s_mov_b32 m0, s28
	v_mfma_f32_16x16x32_bf16 v[72:75], v[158:161], v[222:225], v[72:75]
	global_load_lds_dwordx4 v0, s[48:49]
	v_mfma_f32_16x16x32_bf16 v[76:79], v[166:169], v[222:225], v[76:79]
	v_mfma_f32_16x16x32_bf16 v[80:83], v[214:217], v[222:225], v[80:83]
	v_mfma_f32_16x16x32_bf16 v[32:35], v[218:221], v[222:225], v[32:35]
	ds_read_b128 v[222:225], v18
	s_waitcnt lgkmcnt(3)
	v_mfma_f32_16x16x32_bf16 v[88:91], v[158:161], v[226:229], v[88:91]
	s_mov_b32 m0, s29
	v_mfma_f32_16x16x32_bf16 v[92:95], v[166:169], v[226:229], v[92:95]
	global_load_lds_dwordx4 v2, s[46:47]
	v_mfma_f32_16x16x32_bf16 v[96:99], v[214:217], v[226:229], v[96:99]
	v_mfma_f32_16x16x32_bf16 v[36:39], v[218:221], v[226:229], v[36:39]
	ds_read_b128 v[226:229], v19
	s_waitcnt lgkmcnt(3)
	v_mfma_f32_16x16x32_bf16 v[104:107], v[158:161], v[162:165], v[104:107]
	s_waitcnt lgkmcnt(2)
	v_mfma_f32_16x16x32_bf16 v[116:119], v[158:161], v[178:181], v[116:119]
	s_waitcnt lgkmcnt(1)
	s_mov_b32 m0, s30
	v_mfma_f32_16x16x32_bf16 v[128:131], v[158:161], v[222:225], v[128:131]
	global_load_lds_dwordx4 v2, s[48:49]
	s_waitcnt lgkmcnt(0)
	v_mfma_f32_16x16x32_bf16 v[100:103], v[158:161], v[226:229], v[100:103]
	ds_read_b128 v[158:161], v20
	v_mfma_f32_16x16x32_bf16 v[108:111], v[166:169], v[162:165], v[108:111]
	v_mfma_f32_16x16x32_bf16 v[120:123], v[166:169], v[178:181], v[120:123]
	v_mfma_f32_16x16x32_bf16 v[132:135], v[166:169], v[222:225], v[132:135]
	s_mov_b32 m0, s31
	v_mfma_f32_16x16x32_bf16 v[140:143], v[166:169], v[226:229], v[140:143]
	global_load_lds_dwordx4 v4, s[46:47]
	ds_read_b128 v[166:169], v24
	v_mfma_f32_16x16x32_bf16 v[112:115], v[214:217], v[162:165], v[112:115]
	v_mfma_f32_16x16x32_bf16 v[52:55], v[218:221], v[162:165], v[52:55]
	ds_read_b128 v[162:165], v21
	v_mfma_f32_16x16x32_bf16 v[124:127], v[214:217], v[178:181], v[124:127]
	v_mfma_f32_16x16x32_bf16 v[68:71], v[218:221], v[178:181], v[68:71]
	ds_read_b128 v[178:181], v25
	s_mov_b32 m0, s34
	v_mfma_f32_16x16x32_bf16 v[136:139], v[214:217], v[222:225], v[136:139]
	global_load_lds_dwordx4 v4, s[48:49]
	v_mfma_f32_16x16x32_bf16 v[84:87], v[218:221], v[222:225], v[84:87]
	ds_read_b128 v[222:225], v26
	v_mfma_f32_16x16x32_bf16 v[150:153], v[214:217], v[226:229], v[150:153]
	ds_read_b128 v[214:217], v23
	v_mfma_f32_16x16x32_bf16 v[154:157], v[218:221], v[226:229], v[154:157]
	ds_read_b128 v[218:221], v22
	ds_read_b128 v[226:229], v27
	s_waitcnt lgkmcnt(6)
	v_mfma_f32_16x16x32_bf16 v[40:43], v[158:161], v[166:169], v[40:43]
	s_waitcnt lgkmcnt(5)
	s_mov_b32 m0, s35
	v_mfma_f32_16x16x32_bf16 v[44:47], v[162:165], v[166:169], v[44:47]
	global_load_lds_dwordx4 v146, s[46:47]
	s_waitcnt lgkmcnt(4)
	v_mfma_f32_16x16x32_bf16 v[56:59], v[158:161], v[178:181], v[56:59]
	v_mfma_f32_16x16x32_bf16 v[60:63], v[162:165], v[178:181], v[60:63]
	s_waitcnt lgkmcnt(3)
	v_mfma_f32_16x16x32_bf16 v[72:75], v[158:161], v[222:225], v[72:75]
	v_mfma_f32_16x16x32_bf16 v[76:79], v[162:165], v[222:225], v[76:79]
	s_waitcnt lgkmcnt(2)
	s_mov_b32 m0, s36
	v_mfma_f32_16x16x32_bf16 v[48:51], v[214:217], v[166:169], v[48:51]
	global_load_lds_dwordx4 v146, s[48:49]
	s_waitcnt lgkmcnt(1)
	v_mfma_f32_16x16x32_bf16 v[174:177], v[218:221], v[166:169], v[174:177]
	ds_read_b128 v[166:169], v28
	v_mfma_f32_16x16x32_bf16 v[64:67], v[214:217], v[178:181], v[64:67]
	v_mfma_f32_16x16x32_bf16 v[170:173], v[218:221], v[178:181], v[170:173]
	ds_read_b128 v[178:181], v29
	v_mfma_f32_16x16x32_bf16 v[80:83], v[214:217], v[222:225], v[80:83]
	v_mfma_f32_16x16x32_bf16 v[32:35], v[218:221], v[222:225], v[32:35]
	ds_read_b128 v[222:225], v30
	s_waitcnt lgkmcnt(3)
	v_mfma_f32_16x16x32_bf16 v[88:91], v[158:161], v[226:229], v[88:91]
	v_mfma_f32_16x16x32_bf16 v[92:95], v[162:165], v[226:229], v[92:95]
	v_mfma_f32_16x16x32_bf16 v[96:99], v[214:217], v[226:229], v[96:99]
	v_mfma_f32_16x16x32_bf16 v[36:39], v[218:221], v[226:229], v[36:39]
	ds_read_b128 v[226:229], v31
	s_waitcnt lgkmcnt(3)
	v_mfma_f32_16x16x32_bf16 v[104:107], v[158:161], v[166:169], v[104:107]
	v_mfma_f32_16x16x32_bf16 v[108:111], v[162:165], v[166:169], v[108:111]
	v_mfma_f32_16x16x32_bf16 v[112:115], v[214:217], v[166:169], v[112:115]
	v_mfma_f32_16x16x32_bf16 v[52:55], v[218:221], v[166:169], v[52:55]
	s_waitcnt lgkmcnt(2)
	v_mfma_f32_16x16x32_bf16 v[116:119], v[158:161], v[178:181], v[116:119]
	v_mfma_f32_16x16x32_bf16 v[120:123], v[162:165], v[178:181], v[120:123]
	v_mfma_f32_16x16x32_bf16 v[124:127], v[214:217], v[178:181], v[124:127]
	v_mfma_f32_16x16x32_bf16 v[68:71], v[218:221], v[178:181], v[68:71]
	s_waitcnt lgkmcnt(1)
	v_mfma_f32_16x16x32_bf16 v[128:131], v[158:161], v[222:225], v[128:131]
	v_mfma_f32_16x16x32_bf16 v[132:135], v[162:165], v[222:225], v[132:135]
	v_mfma_f32_16x16x32_bf16 v[136:139], v[214:217], v[222:225], v[136:139]
	v_mfma_f32_16x16x32_bf16 v[84:87], v[218:221], v[222:225], v[84:87]
	s_waitcnt lgkmcnt(0)
	v_mfma_f32_16x16x32_bf16 v[100:103], v[158:161], v[226:229], v[100:103]
	v_mfma_f32_16x16x32_bf16 v[140:143], v[162:165], v[226:229], v[140:143]
	v_mfma_f32_16x16x32_bf16 v[150:153], v[214:217], v[226:229], v[150:153]
	v_mfma_f32_16x16x32_bf16 v[154:157], v[218:221], v[226:229], v[154:157]
	s_add_u32 s46, s0, 0x1280
	s_addc_u32 s47, s1, 0
	s_add_u32 s48, s14, 0x1280
	s_waitcnt vmcnt(0)
	s_barrier
	s_addc_u32 s49, s15, 0
	ds_read_b128 v[158:161], v7 offset:32768
	ds_read_b128 v[162:165], v6
	ds_read_b128 v[166:169], v7 offset:34816
	ds_read_b128 v[178:181], v6 offset:2048
	ds_read_b128 v[214:217], v7 offset:36864
	ds_read_b128 v[218:221], v7 offset:38912
	ds_read_b128 v[222:225], v6 offset:4096
	ds_read_b128 v[226:229], v6 offset:6144
	s_waitcnt lgkmcnt(6)
	v_mfma_f32_16x16x32_bf16 v[40:43], v[158:161], v[162:165], v[40:43]
	s_waitcnt lgkmcnt(5)
	v_mfma_f32_16x16x32_bf16 v[44:47], v[166:169], v[162:165], v[44:47]
	s_waitcnt lgkmcnt(4)
	v_mfma_f32_16x16x32_bf16 v[56:59], v[158:161], v[178:181], v[56:59]
	s_mov_b32 m0, s38
	v_mfma_f32_16x16x32_bf16 v[60:63], v[166:169], v[178:181], v[60:63]
	global_load_lds_dwordx4 v0, s[46:47]
	s_waitcnt lgkmcnt(3)
	v_mfma_f32_16x16x32_bf16 v[48:51], v[214:217], v[162:165], v[48:51]
	v_mfma_f32_16x16x32_bf16 v[64:67], v[214:217], v[178:181], v[64:67]
	s_waitcnt lgkmcnt(2)
	v_mfma_f32_16x16x32_bf16 v[174:177], v[218:221], v[162:165], v[174:177]
	ds_read_b128 v[162:165], v6 offset:8192
	v_mfma_f32_16x16x32_bf16 v[170:173], v[218:221], v[178:181], v[170:173]
	ds_read_b128 v[178:181], v6 offset:10240
	s_waitcnt lgkmcnt(3)
	s_mov_b32 m0, s37
	v_mfma_f32_16x16x32_bf16 v[72:75], v[158:161], v[222:225], v[72:75]
	global_load_lds_dwordx4 v0, s[48:49]
	v_mfma_f32_16x16x32_bf16 v[76:79], v[166:169], v[222:225], v[76:79]
	v_mfma_f32_16x16x32_bf16 v[80:83], v[214:217], v[222:225], v[80:83]
	v_mfma_f32_16x16x32_bf16 v[32:35], v[218:221], v[222:225], v[32:35]
	ds_read_b128 v[222:225], v6 offset:12288
	s_waitcnt lgkmcnt(3)
	v_mfma_f32_16x16x32_bf16 v[88:91], v[158:161], v[226:229], v[88:91]
	s_mov_b32 m0, s39
	v_mfma_f32_16x16x32_bf16 v[92:95], v[166:169], v[226:229], v[92:95]
	global_load_lds_dwordx4 v2, s[46:47]
	v_mfma_f32_16x16x32_bf16 v[96:99], v[214:217], v[226:229], v[96:99]
	v_mfma_f32_16x16x32_bf16 v[36:39], v[218:221], v[226:229], v[36:39]
	ds_read_b128 v[226:229], v6 offset:14336
	s_waitcnt lgkmcnt(3)
	v_mfma_f32_16x16x32_bf16 v[104:107], v[158:161], v[162:165], v[104:107]
	s_waitcnt lgkmcnt(2)
	v_mfma_f32_16x16x32_bf16 v[116:119], v[158:161], v[178:181], v[116:119]
	s_waitcnt lgkmcnt(1)
	s_mov_b32 m0, s40
	v_mfma_f32_16x16x32_bf16 v[128:131], v[158:161], v[222:225], v[128:131]
	global_load_lds_dwordx4 v2, s[48:49]
	s_waitcnt lgkmcnt(0)
	v_mfma_f32_16x16x32_bf16 v[100:103], v[158:161], v[226:229], v[100:103]
	ds_read_b128 v[158:161], v7 offset:33792
	v_mfma_f32_16x16x32_bf16 v[108:111], v[166:169], v[162:165], v[108:111]
	v_mfma_f32_16x16x32_bf16 v[120:123], v[166:169], v[178:181], v[120:123]
	v_mfma_f32_16x16x32_bf16 v[132:135], v[166:169], v[222:225], v[132:135]
	s_mov_b32 m0, s41
	v_mfma_f32_16x16x32_bf16 v[140:143], v[166:169], v[226:229], v[140:143]
	global_load_lds_dwordx4 v4, s[46:47]
	ds_read_b128 v[166:169], v6 offset:1024
	v_mfma_f32_16x16x32_bf16 v[112:115], v[214:217], v[162:165], v[112:115]
	v_mfma_f32_16x16x32_bf16 v[52:55], v[218:221], v[162:165], v[52:55]
	ds_read_b128 v[162:165], v7 offset:35840
	v_mfma_f32_16x16x32_bf16 v[124:127], v[214:217], v[178:181], v[124:127]
	v_mfma_f32_16x16x32_bf16 v[68:71], v[218:221], v[178:181], v[68:71]
	ds_read_b128 v[178:181], v6 offset:3072
	s_mov_b32 m0, s42
	v_mfma_f32_16x16x32_bf16 v[136:139], v[214:217], v[222:225], v[136:139]
	global_load_lds_dwordx4 v4, s[48:49]
	v_mfma_f32_16x16x32_bf16 v[84:87], v[218:221], v[222:225], v[84:87]
	ds_read_b128 v[222:225], v6 offset:5120
	v_mfma_f32_16x16x32_bf16 v[150:153], v[214:217], v[226:229], v[150:153]
	ds_read_b128 v[214:217], v7 offset:37888
	v_mfma_f32_16x16x32_bf16 v[154:157], v[218:221], v[226:229], v[154:157]
	ds_read_b128 v[218:221], v7 offset:39936
	ds_read_b128 v[226:229], v6 offset:7168
	s_waitcnt lgkmcnt(6)
	v_mfma_f32_16x16x32_bf16 v[40:43], v[158:161], v[166:169], v[40:43]
	s_waitcnt lgkmcnt(5)
	s_mov_b32 m0, s43
	v_mfma_f32_16x16x32_bf16 v[44:47], v[162:165], v[166:169], v[44:47]
	global_load_lds_dwordx4 v146, s[46:47]
	s_waitcnt lgkmcnt(4)
	v_mfma_f32_16x16x32_bf16 v[56:59], v[158:161], v[178:181], v[56:59]
	v_mfma_f32_16x16x32_bf16 v[60:63], v[162:165], v[178:181], v[60:63]
	s_waitcnt lgkmcnt(3)
	v_mfma_f32_16x16x32_bf16 v[72:75], v[158:161], v[222:225], v[72:75]
	v_mfma_f32_16x16x32_bf16 v[76:79], v[162:165], v[222:225], v[76:79]
	s_waitcnt lgkmcnt(2)
	s_mov_b32 m0, s44
	v_mfma_f32_16x16x32_bf16 v[48:51], v[214:217], v[166:169], v[48:51]
	global_load_lds_dwordx4 v146, s[48:49]
	s_waitcnt lgkmcnt(1)
	v_mfma_f32_16x16x32_bf16 v[174:177], v[218:221], v[166:169], v[174:177]
	ds_read_b128 v[166:169], v6 offset:9216
	v_mfma_f32_16x16x32_bf16 v[64:67], v[214:217], v[178:181], v[64:67]
	v_mfma_f32_16x16x32_bf16 v[170:173], v[218:221], v[178:181], v[170:173]
	ds_read_b128 v[178:181], v6 offset:11264
	v_mfma_f32_16x16x32_bf16 v[80:83], v[214:217], v[222:225], v[80:83]
	v_mfma_f32_16x16x32_bf16 v[32:35], v[218:221], v[222:225], v[32:35]
	ds_read_b128 v[222:225], v6 offset:13312
	s_waitcnt lgkmcnt(3)
	v_mfma_f32_16x16x32_bf16 v[88:91], v[158:161], v[226:229], v[88:91]
	v_mfma_f32_16x16x32_bf16 v[92:95], v[162:165], v[226:229], v[92:95]
	v_mfma_f32_16x16x32_bf16 v[96:99], v[214:217], v[226:229], v[96:99]
	v_mfma_f32_16x16x32_bf16 v[36:39], v[218:221], v[226:229], v[36:39]
	ds_read_b128 v[226:229], v6 offset:15360
	s_waitcnt lgkmcnt(3)
	v_mfma_f32_16x16x32_bf16 v[104:107], v[158:161], v[166:169], v[104:107]
	v_mfma_f32_16x16x32_bf16 v[108:111], v[162:165], v[166:169], v[108:111]
	v_mfma_f32_16x16x32_bf16 v[112:115], v[214:217], v[166:169], v[112:115]
	v_mfma_f32_16x16x32_bf16 v[52:55], v[218:221], v[166:169], v[52:55]
	s_waitcnt lgkmcnt(2)
	v_mfma_f32_16x16x32_bf16 v[116:119], v[158:161], v[178:181], v[116:119]
	v_mfma_f32_16x16x32_bf16 v[120:123], v[162:165], v[178:181], v[120:123]
	v_mfma_f32_16x16x32_bf16 v[124:127], v[214:217], v[178:181], v[124:127]
	v_mfma_f32_16x16x32_bf16 v[68:71], v[218:221], v[178:181], v[68:71]
	s_waitcnt lgkmcnt(1)
	v_mfma_f32_16x16x32_bf16 v[128:131], v[158:161], v[222:225], v[128:131]
	v_mfma_f32_16x16x32_bf16 v[132:135], v[162:165], v[222:225], v[132:135]
	v_mfma_f32_16x16x32_bf16 v[136:139], v[214:217], v[222:225], v[136:139]
	v_mfma_f32_16x16x32_bf16 v[84:87], v[218:221], v[222:225], v[84:87]
	s_waitcnt lgkmcnt(0)
	v_mfma_f32_16x16x32_bf16 v[100:103], v[158:161], v[226:229], v[100:103]
	v_mfma_f32_16x16x32_bf16 v[140:143], v[162:165], v[226:229], v[140:143]
	v_mfma_f32_16x16x32_bf16 v[150:153], v[214:217], v[226:229], v[150:153]
	v_mfma_f32_16x16x32_bf16 v[154:157], v[218:221], v[226:229], v[154:157]
	s_add_u32 s46, s0, 0x1300
	s_addc_u32 s47, s1, 0
	s_add_u32 s48, s14, 0x1300
	s_waitcnt vmcnt(0)
	s_barrier
	s_addc_u32 s49, s15, 0
	ds_read_b128 v[158:161], v8
	ds_read_b128 v[162:165], v12
	ds_read_b128 v[166:169], v9
	ds_read_b128 v[178:181], v13
	ds_read_b128 v[214:217], v11
	ds_read_b128 v[218:221], v10
	ds_read_b128 v[222:225], v14
	ds_read_b128 v[226:229], v15
	s_waitcnt lgkmcnt(6)
	v_mfma_f32_16x16x32_bf16 v[40:43], v[158:161], v[162:165], v[40:43]
	s_waitcnt lgkmcnt(5)
	v_mfma_f32_16x16x32_bf16 v[44:47], v[166:169], v[162:165], v[44:47]
	s_waitcnt lgkmcnt(4)
	v_mfma_f32_16x16x32_bf16 v[56:59], v[158:161], v[178:181], v[56:59]
	s_mov_b32 m0, s27
	v_mfma_f32_16x16x32_bf16 v[60:63], v[166:169], v[178:181], v[60:63]
	global_load_lds_dwordx4 v0, s[46:47]
	s_waitcnt lgkmcnt(3)
	v_mfma_f32_16x16x32_bf16 v[48:51], v[214:217], v[162:165], v[48:51]
	v_mfma_f32_16x16x32_bf16 v[64:67], v[214:217], v[178:181], v[64:67]
	s_waitcnt lgkmcnt(2)
	v_mfma_f32_16x16x32_bf16 v[174:177], v[218:221], v[162:165], v[174:177]
	ds_read_b128 v[162:165], v16
	v_mfma_f32_16x16x32_bf16 v[170:173], v[218:221], v[178:181], v[170:173]
	ds_read_b128 v[178:181], v17
	s_waitcnt lgkmcnt(3)
	s_mov_b32 m0, s28
	v_mfma_f32_16x16x32_bf16 v[72:75], v[158:161], v[222:225], v[72:75]
	global_load_lds_dwordx4 v0, s[48:49]
	v_mfma_f32_16x16x32_bf16 v[76:79], v[166:169], v[222:225], v[76:79]
	v_mfma_f32_16x16x32_bf16 v[80:83], v[214:217], v[222:225], v[80:83]
	v_mfma_f32_16x16x32_bf16 v[32:35], v[218:221], v[222:225], v[32:35]
	ds_read_b128 v[222:225], v18
	s_waitcnt lgkmcnt(3)
	v_mfma_f32_16x16x32_bf16 v[88:91], v[158:161], v[226:229], v[88:91]
	s_mov_b32 m0, s29
	v_mfma_f32_16x16x32_bf16 v[92:95], v[166:169], v[226:229], v[92:95]
	global_load_lds_dwordx4 v2, s[46:47]
	v_mfma_f32_16x16x32_bf16 v[96:99], v[214:217], v[226:229], v[96:99]
	v_mfma_f32_16x16x32_bf16 v[36:39], v[218:221], v[226:229], v[36:39]
	ds_read_b128 v[226:229], v19
	s_waitcnt lgkmcnt(3)
	v_mfma_f32_16x16x32_bf16 v[104:107], v[158:161], v[162:165], v[104:107]
	s_waitcnt lgkmcnt(2)
	v_mfma_f32_16x16x32_bf16 v[116:119], v[158:161], v[178:181], v[116:119]
	s_waitcnt lgkmcnt(1)
	s_mov_b32 m0, s30
	v_mfma_f32_16x16x32_bf16 v[128:131], v[158:161], v[222:225], v[128:131]
	global_load_lds_dwordx4 v2, s[48:49]
	s_waitcnt lgkmcnt(0)
	v_mfma_f32_16x16x32_bf16 v[100:103], v[158:161], v[226:229], v[100:103]
	ds_read_b128 v[158:161], v20
	v_mfma_f32_16x16x32_bf16 v[108:111], v[166:169], v[162:165], v[108:111]
	v_mfma_f32_16x16x32_bf16 v[120:123], v[166:169], v[178:181], v[120:123]
	v_mfma_f32_16x16x32_bf16 v[132:135], v[166:169], v[222:225], v[132:135]
	s_mov_b32 m0, s31
	v_mfma_f32_16x16x32_bf16 v[140:143], v[166:169], v[226:229], v[140:143]
	global_load_lds_dwordx4 v4, s[46:47]
	ds_read_b128 v[166:169], v24
	v_mfma_f32_16x16x32_bf16 v[112:115], v[214:217], v[162:165], v[112:115]
	v_mfma_f32_16x16x32_bf16 v[52:55], v[218:221], v[162:165], v[52:55]
	ds_read_b128 v[162:165], v21
	v_mfma_f32_16x16x32_bf16 v[124:127], v[214:217], v[178:181], v[124:127]
	v_mfma_f32_16x16x32_bf16 v[68:71], v[218:221], v[178:181], v[68:71]
	ds_read_b128 v[178:181], v25
	s_mov_b32 m0, s34
	v_mfma_f32_16x16x32_bf16 v[136:139], v[214:217], v[222:225], v[136:139]
	global_load_lds_dwordx4 v4, s[48:49]
	v_mfma_f32_16x16x32_bf16 v[84:87], v[218:221], v[222:225], v[84:87]
	ds_read_b128 v[222:225], v26
	v_mfma_f32_16x16x32_bf16 v[150:153], v[214:217], v[226:229], v[150:153]
	ds_read_b128 v[214:217], v23
	v_mfma_f32_16x16x32_bf16 v[154:157], v[218:221], v[226:229], v[154:157]
	ds_read_b128 v[218:221], v22
	ds_read_b128 v[226:229], v27
	s_waitcnt lgkmcnt(6)
	v_mfma_f32_16x16x32_bf16 v[40:43], v[158:161], v[166:169], v[40:43]
	s_waitcnt lgkmcnt(5)
	s_mov_b32 m0, s35
	v_mfma_f32_16x16x32_bf16 v[44:47], v[162:165], v[166:169], v[44:47]
	global_load_lds_dwordx4 v146, s[46:47]
	s_waitcnt lgkmcnt(4)
	v_mfma_f32_16x16x32_bf16 v[56:59], v[158:161], v[178:181], v[56:59]
	v_mfma_f32_16x16x32_bf16 v[60:63], v[162:165], v[178:181], v[60:63]
	s_waitcnt lgkmcnt(3)
	v_mfma_f32_16x16x32_bf16 v[72:75], v[158:161], v[222:225], v[72:75]
	v_mfma_f32_16x16x32_bf16 v[76:79], v[162:165], v[222:225], v[76:79]
	s_waitcnt lgkmcnt(2)
	s_mov_b32 m0, s36
	v_mfma_f32_16x16x32_bf16 v[48:51], v[214:217], v[166:169], v[48:51]
	global_load_lds_dwordx4 v146, s[48:49]
	s_waitcnt lgkmcnt(1)
	v_mfma_f32_16x16x32_bf16 v[174:177], v[218:221], v[166:169], v[174:177]
	ds_read_b128 v[166:169], v28
	v_mfma_f32_16x16x32_bf16 v[64:67], v[214:217], v[178:181], v[64:67]
	v_mfma_f32_16x16x32_bf16 v[170:173], v[218:221], v[178:181], v[170:173]
	ds_read_b128 v[178:181], v29
	v_mfma_f32_16x16x32_bf16 v[80:83], v[214:217], v[222:225], v[80:83]
	v_mfma_f32_16x16x32_bf16 v[32:35], v[218:221], v[222:225], v[32:35]
	ds_read_b128 v[222:225], v30
	s_waitcnt lgkmcnt(3)
	v_mfma_f32_16x16x32_bf16 v[88:91], v[158:161], v[226:229], v[88:91]
	v_mfma_f32_16x16x32_bf16 v[92:95], v[162:165], v[226:229], v[92:95]
	v_mfma_f32_16x16x32_bf16 v[96:99], v[214:217], v[226:229], v[96:99]
	v_mfma_f32_16x16x32_bf16 v[36:39], v[218:221], v[226:229], v[36:39]
	ds_read_b128 v[226:229], v31
	s_waitcnt lgkmcnt(3)
	v_mfma_f32_16x16x32_bf16 v[104:107], v[158:161], v[166:169], v[104:107]
	v_mfma_f32_16x16x32_bf16 v[108:111], v[162:165], v[166:169], v[108:111]
	v_mfma_f32_16x16x32_bf16 v[112:115], v[214:217], v[166:169], v[112:115]
	v_mfma_f32_16x16x32_bf16 v[52:55], v[218:221], v[166:169], v[52:55]
	s_waitcnt lgkmcnt(2)
	v_mfma_f32_16x16x32_bf16 v[116:119], v[158:161], v[178:181], v[116:119]
	v_mfma_f32_16x16x32_bf16 v[120:123], v[162:165], v[178:181], v[120:123]
	v_mfma_f32_16x16x32_bf16 v[124:127], v[214:217], v[178:181], v[124:127]
	v_mfma_f32_16x16x32_bf16 v[68:71], v[218:221], v[178:181], v[68:71]
	s_waitcnt lgkmcnt(1)
	v_mfma_f32_16x16x32_bf16 v[128:131], v[158:161], v[222:225], v[128:131]
	v_mfma_f32_16x16x32_bf16 v[132:135], v[162:165], v[222:225], v[132:135]
	v_mfma_f32_16x16x32_bf16 v[136:139], v[214:217], v[222:225], v[136:139]
	v_mfma_f32_16x16x32_bf16 v[84:87], v[218:221], v[222:225], v[84:87]
	s_waitcnt lgkmcnt(0)
	v_mfma_f32_16x16x32_bf16 v[100:103], v[158:161], v[226:229], v[100:103]
	v_mfma_f32_16x16x32_bf16 v[140:143], v[162:165], v[226:229], v[140:143]
	v_mfma_f32_16x16x32_bf16 v[150:153], v[214:217], v[226:229], v[150:153]
	v_mfma_f32_16x16x32_bf16 v[154:157], v[218:221], v[226:229], v[154:157]
	s_add_u32 s46, s0, 0x1380
	s_addc_u32 s47, s1, 0
	s_add_u32 s48, s14, 0x1380
	s_waitcnt vmcnt(0)
	s_barrier
	s_addc_u32 s49, s15, 0
	ds_read_b128 v[158:161], v7 offset:32768
	ds_read_b128 v[162:165], v6
	ds_read_b128 v[166:169], v7 offset:34816
	ds_read_b128 v[178:181], v6 offset:2048
	ds_read_b128 v[214:217], v7 offset:36864
	ds_read_b128 v[218:221], v7 offset:38912
	ds_read_b128 v[222:225], v6 offset:4096
	ds_read_b128 v[226:229], v6 offset:6144
	s_waitcnt lgkmcnt(6)
	v_mfma_f32_16x16x32_bf16 v[40:43], v[158:161], v[162:165], v[40:43]
	s_waitcnt lgkmcnt(5)
	v_mfma_f32_16x16x32_bf16 v[44:47], v[166:169], v[162:165], v[44:47]
	s_waitcnt lgkmcnt(4)
	v_mfma_f32_16x16x32_bf16 v[56:59], v[158:161], v[178:181], v[56:59]
	s_mov_b32 m0, s38
	v_mfma_f32_16x16x32_bf16 v[60:63], v[166:169], v[178:181], v[60:63]
	global_load_lds_dwordx4 v0, s[46:47]
	s_waitcnt lgkmcnt(3)
	v_mfma_f32_16x16x32_bf16 v[48:51], v[214:217], v[162:165], v[48:51]
	v_mfma_f32_16x16x32_bf16 v[64:67], v[214:217], v[178:181], v[64:67]
	s_waitcnt lgkmcnt(2)
	v_mfma_f32_16x16x32_bf16 v[174:177], v[218:221], v[162:165], v[174:177]
	ds_read_b128 v[162:165], v6 offset:8192
	v_mfma_f32_16x16x32_bf16 v[170:173], v[218:221], v[178:181], v[170:173]
	ds_read_b128 v[178:181], v6 offset:10240
	s_waitcnt lgkmcnt(3)
	s_mov_b32 m0, s37
	v_mfma_f32_16x16x32_bf16 v[72:75], v[158:161], v[222:225], v[72:75]
	global_load_lds_dwordx4 v0, s[48:49]
	v_mfma_f32_16x16x32_bf16 v[76:79], v[166:169], v[222:225], v[76:79]
	v_mfma_f32_16x16x32_bf16 v[80:83], v[214:217], v[222:225], v[80:83]
	v_mfma_f32_16x16x32_bf16 v[32:35], v[218:221], v[222:225], v[32:35]
	ds_read_b128 v[222:225], v6 offset:12288
	s_waitcnt lgkmcnt(3)
	v_mfma_f32_16x16x32_bf16 v[88:91], v[158:161], v[226:229], v[88:91]
	s_mov_b32 m0, s39
	v_mfma_f32_16x16x32_bf16 v[92:95], v[166:169], v[226:229], v[92:95]
	global_load_lds_dwordx4 v2, s[46:47]
	v_mfma_f32_16x16x32_bf16 v[96:99], v[214:217], v[226:229], v[96:99]
	v_mfma_f32_16x16x32_bf16 v[36:39], v[218:221], v[226:229], v[36:39]
	ds_read_b128 v[226:229], v6 offset:14336
	s_waitcnt lgkmcnt(3)
	v_mfma_f32_16x16x32_bf16 v[104:107], v[158:161], v[162:165], v[104:107]
	s_waitcnt lgkmcnt(2)
	v_mfma_f32_16x16x32_bf16 v[116:119], v[158:161], v[178:181], v[116:119]
	s_waitcnt lgkmcnt(1)
	s_mov_b32 m0, s40
	v_mfma_f32_16x16x32_bf16 v[128:131], v[158:161], v[222:225], v[128:131]
	global_load_lds_dwordx4 v2, s[48:49]
	s_waitcnt lgkmcnt(0)
	v_mfma_f32_16x16x32_bf16 v[100:103], v[158:161], v[226:229], v[100:103]
	ds_read_b128 v[158:161], v7 offset:33792
	v_mfma_f32_16x16x32_bf16 v[108:111], v[166:169], v[162:165], v[108:111]
	v_mfma_f32_16x16x32_bf16 v[120:123], v[166:169], v[178:181], v[120:123]
	v_mfma_f32_16x16x32_bf16 v[132:135], v[166:169], v[222:225], v[132:135]
	s_mov_b32 m0, s41
	v_mfma_f32_16x16x32_bf16 v[140:143], v[166:169], v[226:229], v[140:143]
	global_load_lds_dwordx4 v4, s[46:47]
	ds_read_b128 v[166:169], v6 offset:1024
	v_mfma_f32_16x16x32_bf16 v[112:115], v[214:217], v[162:165], v[112:115]
	v_mfma_f32_16x16x32_bf16 v[52:55], v[218:221], v[162:165], v[52:55]
	ds_read_b128 v[162:165], v7 offset:35840
	v_mfma_f32_16x16x32_bf16 v[124:127], v[214:217], v[178:181], v[124:127]
	v_mfma_f32_16x16x32_bf16 v[68:71], v[218:221], v[178:181], v[68:71]
	ds_read_b128 v[178:181], v6 offset:3072
	s_mov_b32 m0, s42
	v_mfma_f32_16x16x32_bf16 v[136:139], v[214:217], v[222:225], v[136:139]
	global_load_lds_dwordx4 v4, s[48:49]
	v_mfma_f32_16x16x32_bf16 v[84:87], v[218:221], v[222:225], v[84:87]
	ds_read_b128 v[222:225], v6 offset:5120
	v_mfma_f32_16x16x32_bf16 v[150:153], v[214:217], v[226:229], v[150:153]
	ds_read_b128 v[214:217], v7 offset:37888
	v_mfma_f32_16x16x32_bf16 v[154:157], v[218:221], v[226:229], v[154:157]
	ds_read_b128 v[218:221], v7 offset:39936
	ds_read_b128 v[226:229], v6 offset:7168
	s_waitcnt lgkmcnt(6)
	v_mfma_f32_16x16x32_bf16 v[40:43], v[158:161], v[166:169], v[40:43]
	s_waitcnt lgkmcnt(5)
	s_mov_b32 m0, s43
	v_mfma_f32_16x16x32_bf16 v[44:47], v[162:165], v[166:169], v[44:47]
	global_load_lds_dwordx4 v146, s[46:47]
	s_waitcnt lgkmcnt(4)
	v_mfma_f32_16x16x32_bf16 v[56:59], v[158:161], v[178:181], v[56:59]
	v_mfma_f32_16x16x32_bf16 v[60:63], v[162:165], v[178:181], v[60:63]
	s_waitcnt lgkmcnt(3)
	v_mfma_f32_16x16x32_bf16 v[72:75], v[158:161], v[222:225], v[72:75]
	v_mfma_f32_16x16x32_bf16 v[76:79], v[162:165], v[222:225], v[76:79]
	s_waitcnt lgkmcnt(2)
	s_mov_b32 m0, s44
	v_mfma_f32_16x16x32_bf16 v[48:51], v[214:217], v[166:169], v[48:51]
	global_load_lds_dwordx4 v146, s[48:49]
	s_waitcnt lgkmcnt(1)
	v_mfma_f32_16x16x32_bf16 v[174:177], v[218:221], v[166:169], v[174:177]
	ds_read_b128 v[166:169], v6 offset:9216
	v_mfma_f32_16x16x32_bf16 v[64:67], v[214:217], v[178:181], v[64:67]
	v_mfma_f32_16x16x32_bf16 v[170:173], v[218:221], v[178:181], v[170:173]
	ds_read_b128 v[178:181], v6 offset:11264
	v_mfma_f32_16x16x32_bf16 v[80:83], v[214:217], v[222:225], v[80:83]
	v_mfma_f32_16x16x32_bf16 v[32:35], v[218:221], v[222:225], v[32:35]
	ds_read_b128 v[222:225], v6 offset:13312
	s_waitcnt lgkmcnt(3)
	v_mfma_f32_16x16x32_bf16 v[88:91], v[158:161], v[226:229], v[88:91]
	v_mfma_f32_16x16x32_bf16 v[92:95], v[162:165], v[226:229], v[92:95]
	v_mfma_f32_16x16x32_bf16 v[96:99], v[214:217], v[226:229], v[96:99]
	v_mfma_f32_16x16x32_bf16 v[36:39], v[218:221], v[226:229], v[36:39]
	ds_read_b128 v[226:229], v6 offset:15360
	s_waitcnt lgkmcnt(3)
	v_mfma_f32_16x16x32_bf16 v[104:107], v[158:161], v[166:169], v[104:107]
	v_mfma_f32_16x16x32_bf16 v[108:111], v[162:165], v[166:169], v[108:111]
	v_mfma_f32_16x16x32_bf16 v[112:115], v[214:217], v[166:169], v[112:115]
	v_mfma_f32_16x16x32_bf16 v[52:55], v[218:221], v[166:169], v[52:55]
	s_waitcnt lgkmcnt(2)
	v_mfma_f32_16x16x32_bf16 v[116:119], v[158:161], v[178:181], v[116:119]
	v_mfma_f32_16x16x32_bf16 v[120:123], v[162:165], v[178:181], v[120:123]
	v_mfma_f32_16x16x32_bf16 v[124:127], v[214:217], v[178:181], v[124:127]
	v_mfma_f32_16x16x32_bf16 v[68:71], v[218:221], v[178:181], v[68:71]
	s_waitcnt lgkmcnt(1)
	v_mfma_f32_16x16x32_bf16 v[128:131], v[158:161], v[222:225], v[128:131]
	v_mfma_f32_16x16x32_bf16 v[132:135], v[162:165], v[222:225], v[132:135]
	v_mfma_f32_16x16x32_bf16 v[136:139], v[214:217], v[222:225], v[136:139]
	v_mfma_f32_16x16x32_bf16 v[84:87], v[218:221], v[222:225], v[84:87]
	s_waitcnt lgkmcnt(0)
	v_mfma_f32_16x16x32_bf16 v[100:103], v[158:161], v[226:229], v[100:103]
	v_mfma_f32_16x16x32_bf16 v[140:143], v[162:165], v[226:229], v[140:143]
	v_mfma_f32_16x16x32_bf16 v[150:153], v[214:217], v[226:229], v[150:153]
	v_mfma_f32_16x16x32_bf16 v[154:157], v[218:221], v[226:229], v[154:157]
	s_add_u32 s46, s0, 0x1400
	s_addc_u32 s47, s1, 0
	s_add_u32 s48, s14, 0x1400
	s_waitcnt vmcnt(0)
	s_barrier
	s_addc_u32 s49, s15, 0
	ds_read_b128 v[158:161], v8
	ds_read_b128 v[162:165], v12
	ds_read_b128 v[166:169], v9
	ds_read_b128 v[178:181], v13
	ds_read_b128 v[214:217], v11
	ds_read_b128 v[218:221], v10
	ds_read_b128 v[222:225], v14
	ds_read_b128 v[226:229], v15
	s_waitcnt lgkmcnt(6)
	v_mfma_f32_16x16x32_bf16 v[40:43], v[158:161], v[162:165], v[40:43]
	s_waitcnt lgkmcnt(5)
	v_mfma_f32_16x16x32_bf16 v[44:47], v[166:169], v[162:165], v[44:47]
	s_waitcnt lgkmcnt(4)
	v_mfma_f32_16x16x32_bf16 v[56:59], v[158:161], v[178:181], v[56:59]
	s_mov_b32 m0, s27
	v_mfma_f32_16x16x32_bf16 v[60:63], v[166:169], v[178:181], v[60:63]
	global_load_lds_dwordx4 v0, s[46:47]
	s_waitcnt lgkmcnt(3)
	v_mfma_f32_16x16x32_bf16 v[48:51], v[214:217], v[162:165], v[48:51]
	v_mfma_f32_16x16x32_bf16 v[64:67], v[214:217], v[178:181], v[64:67]
	s_waitcnt lgkmcnt(2)
	v_mfma_f32_16x16x32_bf16 v[174:177], v[218:221], v[162:165], v[174:177]
	ds_read_b128 v[162:165], v16
	v_mfma_f32_16x16x32_bf16 v[170:173], v[218:221], v[178:181], v[170:173]
	ds_read_b128 v[178:181], v17
	s_waitcnt lgkmcnt(3)
	s_mov_b32 m0, s28
	v_mfma_f32_16x16x32_bf16 v[72:75], v[158:161], v[222:225], v[72:75]
	global_load_lds_dwordx4 v0, s[48:49]
	v_mfma_f32_16x16x32_bf16 v[76:79], v[166:169], v[222:225], v[76:79]
	v_mfma_f32_16x16x32_bf16 v[80:83], v[214:217], v[222:225], v[80:83]
	v_mfma_f32_16x16x32_bf16 v[32:35], v[218:221], v[222:225], v[32:35]
	ds_read_b128 v[222:225], v18
	s_waitcnt lgkmcnt(3)
	v_mfma_f32_16x16x32_bf16 v[88:91], v[158:161], v[226:229], v[88:91]
	s_mov_b32 m0, s29
	v_mfma_f32_16x16x32_bf16 v[92:95], v[166:169], v[226:229], v[92:95]
	global_load_lds_dwordx4 v2, s[46:47]
	v_mfma_f32_16x16x32_bf16 v[96:99], v[214:217], v[226:229], v[96:99]
	v_mfma_f32_16x16x32_bf16 v[36:39], v[218:221], v[226:229], v[36:39]
	ds_read_b128 v[226:229], v19
	s_waitcnt lgkmcnt(3)
	v_mfma_f32_16x16x32_bf16 v[104:107], v[158:161], v[162:165], v[104:107]
	s_waitcnt lgkmcnt(2)
	v_mfma_f32_16x16x32_bf16 v[116:119], v[158:161], v[178:181], v[116:119]
	s_waitcnt lgkmcnt(1)
	s_mov_b32 m0, s30
	v_mfma_f32_16x16x32_bf16 v[128:131], v[158:161], v[222:225], v[128:131]
	global_load_lds_dwordx4 v2, s[48:49]
	s_waitcnt lgkmcnt(0)
	v_mfma_f32_16x16x32_bf16 v[100:103], v[158:161], v[226:229], v[100:103]
	ds_read_b128 v[158:161], v20
	v_mfma_f32_16x16x32_bf16 v[108:111], v[166:169], v[162:165], v[108:111]
	v_mfma_f32_16x16x32_bf16 v[120:123], v[166:169], v[178:181], v[120:123]
	v_mfma_f32_16x16x32_bf16 v[132:135], v[166:169], v[222:225], v[132:135]
	s_mov_b32 m0, s31
	v_mfma_f32_16x16x32_bf16 v[140:143], v[166:169], v[226:229], v[140:143]
	global_load_lds_dwordx4 v4, s[46:47]
	ds_read_b128 v[166:169], v24
	v_mfma_f32_16x16x32_bf16 v[112:115], v[214:217], v[162:165], v[112:115]
	v_mfma_f32_16x16x32_bf16 v[52:55], v[218:221], v[162:165], v[52:55]
	ds_read_b128 v[162:165], v21
	v_mfma_f32_16x16x32_bf16 v[124:127], v[214:217], v[178:181], v[124:127]
	v_mfma_f32_16x16x32_bf16 v[68:71], v[218:221], v[178:181], v[68:71]
	ds_read_b128 v[178:181], v25
	s_mov_b32 m0, s34
	v_mfma_f32_16x16x32_bf16 v[136:139], v[214:217], v[222:225], v[136:139]
	global_load_lds_dwordx4 v4, s[48:49]
	v_mfma_f32_16x16x32_bf16 v[84:87], v[218:221], v[222:225], v[84:87]
	ds_read_b128 v[222:225], v26
	v_mfma_f32_16x16x32_bf16 v[150:153], v[214:217], v[226:229], v[150:153]
	ds_read_b128 v[214:217], v23
	v_mfma_f32_16x16x32_bf16 v[154:157], v[218:221], v[226:229], v[154:157]
	ds_read_b128 v[218:221], v22
	ds_read_b128 v[226:229], v27
	s_waitcnt lgkmcnt(6)
	v_mfma_f32_16x16x32_bf16 v[40:43], v[158:161], v[166:169], v[40:43]
	s_waitcnt lgkmcnt(5)
	s_mov_b32 m0, s35
	v_mfma_f32_16x16x32_bf16 v[44:47], v[162:165], v[166:169], v[44:47]
	global_load_lds_dwordx4 v146, s[46:47]
	s_waitcnt lgkmcnt(4)
	v_mfma_f32_16x16x32_bf16 v[56:59], v[158:161], v[178:181], v[56:59]
	v_mfma_f32_16x16x32_bf16 v[60:63], v[162:165], v[178:181], v[60:63]
	s_waitcnt lgkmcnt(3)
	v_mfma_f32_16x16x32_bf16 v[72:75], v[158:161], v[222:225], v[72:75]
	v_mfma_f32_16x16x32_bf16 v[76:79], v[162:165], v[222:225], v[76:79]
	s_waitcnt lgkmcnt(2)
	s_mov_b32 m0, s36
	v_mfma_f32_16x16x32_bf16 v[48:51], v[214:217], v[166:169], v[48:51]
	global_load_lds_dwordx4 v146, s[48:49]
	s_waitcnt lgkmcnt(1)
	v_mfma_f32_16x16x32_bf16 v[174:177], v[218:221], v[166:169], v[174:177]
	ds_read_b128 v[166:169], v28
	v_mfma_f32_16x16x32_bf16 v[64:67], v[214:217], v[178:181], v[64:67]
	v_mfma_f32_16x16x32_bf16 v[170:173], v[218:221], v[178:181], v[170:173]
	ds_read_b128 v[178:181], v29
	v_mfma_f32_16x16x32_bf16 v[80:83], v[214:217], v[222:225], v[80:83]
	v_mfma_f32_16x16x32_bf16 v[32:35], v[218:221], v[222:225], v[32:35]
	ds_read_b128 v[222:225], v30
	s_waitcnt lgkmcnt(3)
	v_mfma_f32_16x16x32_bf16 v[88:91], v[158:161], v[226:229], v[88:91]
	v_mfma_f32_16x16x32_bf16 v[92:95], v[162:165], v[226:229], v[92:95]
	v_mfma_f32_16x16x32_bf16 v[96:99], v[214:217], v[226:229], v[96:99]
	v_mfma_f32_16x16x32_bf16 v[36:39], v[218:221], v[226:229], v[36:39]
	ds_read_b128 v[226:229], v31
	s_waitcnt lgkmcnt(3)
	v_mfma_f32_16x16x32_bf16 v[104:107], v[158:161], v[166:169], v[104:107]
	v_mfma_f32_16x16x32_bf16 v[108:111], v[162:165], v[166:169], v[108:111]
	v_mfma_f32_16x16x32_bf16 v[112:115], v[214:217], v[166:169], v[112:115]
	v_mfma_f32_16x16x32_bf16 v[52:55], v[218:221], v[166:169], v[52:55]
	s_waitcnt lgkmcnt(2)
	v_mfma_f32_16x16x32_bf16 v[116:119], v[158:161], v[178:181], v[116:119]
	v_mfma_f32_16x16x32_bf16 v[120:123], v[162:165], v[178:181], v[120:123]
	v_mfma_f32_16x16x32_bf16 v[124:127], v[214:217], v[178:181], v[124:127]
	v_mfma_f32_16x16x32_bf16 v[68:71], v[218:221], v[178:181], v[68:71]
	s_waitcnt lgkmcnt(1)
	v_mfma_f32_16x16x32_bf16 v[128:131], v[158:161], v[222:225], v[128:131]
	v_mfma_f32_16x16x32_bf16 v[132:135], v[162:165], v[222:225], v[132:135]
	v_mfma_f32_16x16x32_bf16 v[136:139], v[214:217], v[222:225], v[136:139]
	v_mfma_f32_16x16x32_bf16 v[84:87], v[218:221], v[222:225], v[84:87]
	s_waitcnt lgkmcnt(0)
	v_mfma_f32_16x16x32_bf16 v[100:103], v[158:161], v[226:229], v[100:103]
	v_mfma_f32_16x16x32_bf16 v[140:143], v[162:165], v[226:229], v[140:143]
	v_mfma_f32_16x16x32_bf16 v[150:153], v[214:217], v[226:229], v[150:153]
	v_mfma_f32_16x16x32_bf16 v[154:157], v[218:221], v[226:229], v[154:157]
	s_add_u32 s46, s0, 0x1480
	s_addc_u32 s47, s1, 0
	s_add_u32 s48, s14, 0x1480
	s_waitcnt vmcnt(0)
	s_barrier
	s_addc_u32 s49, s15, 0
	ds_read_b128 v[158:161], v7 offset:32768
	ds_read_b128 v[162:165], v6
	ds_read_b128 v[166:169], v7 offset:34816
	ds_read_b128 v[178:181], v6 offset:2048
	ds_read_b128 v[214:217], v7 offset:36864
	ds_read_b128 v[218:221], v7 offset:38912
	ds_read_b128 v[222:225], v6 offset:4096
	ds_read_b128 v[226:229], v6 offset:6144
	s_waitcnt lgkmcnt(6)
	v_mfma_f32_16x16x32_bf16 v[40:43], v[158:161], v[162:165], v[40:43]
	s_waitcnt lgkmcnt(5)
	v_mfma_f32_16x16x32_bf16 v[44:47], v[166:169], v[162:165], v[44:47]
	s_waitcnt lgkmcnt(4)
	v_mfma_f32_16x16x32_bf16 v[56:59], v[158:161], v[178:181], v[56:59]
	s_mov_b32 m0, s38
	v_mfma_f32_16x16x32_bf16 v[60:63], v[166:169], v[178:181], v[60:63]
	global_load_lds_dwordx4 v0, s[46:47]
	s_waitcnt lgkmcnt(3)
	v_mfma_f32_16x16x32_bf16 v[48:51], v[214:217], v[162:165], v[48:51]
	v_mfma_f32_16x16x32_bf16 v[64:67], v[214:217], v[178:181], v[64:67]
	s_waitcnt lgkmcnt(2)
	v_mfma_f32_16x16x32_bf16 v[174:177], v[218:221], v[162:165], v[174:177]
	ds_read_b128 v[162:165], v6 offset:8192
	v_mfma_f32_16x16x32_bf16 v[170:173], v[218:221], v[178:181], v[170:173]
	ds_read_b128 v[178:181], v6 offset:10240
	s_waitcnt lgkmcnt(3)
	s_mov_b32 m0, s37
	v_mfma_f32_16x16x32_bf16 v[72:75], v[158:161], v[222:225], v[72:75]
	global_load_lds_dwordx4 v0, s[48:49]
	v_mfma_f32_16x16x32_bf16 v[76:79], v[166:169], v[222:225], v[76:79]
	v_mfma_f32_16x16x32_bf16 v[80:83], v[214:217], v[222:225], v[80:83]
	v_mfma_f32_16x16x32_bf16 v[32:35], v[218:221], v[222:225], v[32:35]
	ds_read_b128 v[222:225], v6 offset:12288
	s_waitcnt lgkmcnt(3)
	v_mfma_f32_16x16x32_bf16 v[88:91], v[158:161], v[226:229], v[88:91]
	s_mov_b32 m0, s39
	v_mfma_f32_16x16x32_bf16 v[92:95], v[166:169], v[226:229], v[92:95]
	global_load_lds_dwordx4 v2, s[46:47]
	v_mfma_f32_16x16x32_bf16 v[96:99], v[214:217], v[226:229], v[96:99]
	v_mfma_f32_16x16x32_bf16 v[36:39], v[218:221], v[226:229], v[36:39]
	ds_read_b128 v[226:229], v6 offset:14336
	s_waitcnt lgkmcnt(3)
	v_mfma_f32_16x16x32_bf16 v[104:107], v[158:161], v[162:165], v[104:107]
	s_waitcnt lgkmcnt(2)
	v_mfma_f32_16x16x32_bf16 v[116:119], v[158:161], v[178:181], v[116:119]
	s_waitcnt lgkmcnt(1)
	s_mov_b32 m0, s40
	v_mfma_f32_16x16x32_bf16 v[128:131], v[158:161], v[222:225], v[128:131]
	global_load_lds_dwordx4 v2, s[48:49]
	s_waitcnt lgkmcnt(0)
	v_mfma_f32_16x16x32_bf16 v[100:103], v[158:161], v[226:229], v[100:103]
	ds_read_b128 v[158:161], v7 offset:33792
	v_mfma_f32_16x16x32_bf16 v[108:111], v[166:169], v[162:165], v[108:111]
	v_mfma_f32_16x16x32_bf16 v[120:123], v[166:169], v[178:181], v[120:123]
	v_mfma_f32_16x16x32_bf16 v[132:135], v[166:169], v[222:225], v[132:135]
	s_mov_b32 m0, s41
	v_mfma_f32_16x16x32_bf16 v[140:143], v[166:169], v[226:229], v[140:143]
	global_load_lds_dwordx4 v4, s[46:47]
	ds_read_b128 v[166:169], v6 offset:1024
	v_mfma_f32_16x16x32_bf16 v[112:115], v[214:217], v[162:165], v[112:115]
	v_mfma_f32_16x16x32_bf16 v[52:55], v[218:221], v[162:165], v[52:55]
	ds_read_b128 v[162:165], v7 offset:35840
	v_mfma_f32_16x16x32_bf16 v[124:127], v[214:217], v[178:181], v[124:127]
	v_mfma_f32_16x16x32_bf16 v[68:71], v[218:221], v[178:181], v[68:71]
	ds_read_b128 v[178:181], v6 offset:3072
	s_mov_b32 m0, s42
	v_mfma_f32_16x16x32_bf16 v[136:139], v[214:217], v[222:225], v[136:139]
	global_load_lds_dwordx4 v4, s[48:49]
	v_mfma_f32_16x16x32_bf16 v[84:87], v[218:221], v[222:225], v[84:87]
	ds_read_b128 v[222:225], v6 offset:5120
	v_mfma_f32_16x16x32_bf16 v[150:153], v[214:217], v[226:229], v[150:153]
	ds_read_b128 v[214:217], v7 offset:37888
	v_mfma_f32_16x16x32_bf16 v[154:157], v[218:221], v[226:229], v[154:157]
	ds_read_b128 v[218:221], v7 offset:39936
	ds_read_b128 v[226:229], v6 offset:7168
	s_waitcnt lgkmcnt(6)
	v_mfma_f32_16x16x32_bf16 v[40:43], v[158:161], v[166:169], v[40:43]
	s_waitcnt lgkmcnt(5)
	s_mov_b32 m0, s43
	v_mfma_f32_16x16x32_bf16 v[44:47], v[162:165], v[166:169], v[44:47]
	global_load_lds_dwordx4 v146, s[46:47]
	s_waitcnt lgkmcnt(4)
	v_mfma_f32_16x16x32_bf16 v[56:59], v[158:161], v[178:181], v[56:59]
	v_mfma_f32_16x16x32_bf16 v[60:63], v[162:165], v[178:181], v[60:63]
	s_waitcnt lgkmcnt(3)
	v_mfma_f32_16x16x32_bf16 v[72:75], v[158:161], v[222:225], v[72:75]
	v_mfma_f32_16x16x32_bf16 v[76:79], v[162:165], v[222:225], v[76:79]
	s_waitcnt lgkmcnt(2)
	s_mov_b32 m0, s44
	v_mfma_f32_16x16x32_bf16 v[48:51], v[214:217], v[166:169], v[48:51]
	global_load_lds_dwordx4 v146, s[48:49]
	s_waitcnt lgkmcnt(1)
	v_mfma_f32_16x16x32_bf16 v[174:177], v[218:221], v[166:169], v[174:177]
	ds_read_b128 v[166:169], v6 offset:9216
	v_mfma_f32_16x16x32_bf16 v[64:67], v[214:217], v[178:181], v[64:67]
	v_mfma_f32_16x16x32_bf16 v[170:173], v[218:221], v[178:181], v[170:173]
	ds_read_b128 v[178:181], v6 offset:11264
	v_mfma_f32_16x16x32_bf16 v[80:83], v[214:217], v[222:225], v[80:83]
	v_mfma_f32_16x16x32_bf16 v[32:35], v[218:221], v[222:225], v[32:35]
	ds_read_b128 v[222:225], v6 offset:13312
	s_waitcnt lgkmcnt(3)
	v_mfma_f32_16x16x32_bf16 v[88:91], v[158:161], v[226:229], v[88:91]
	v_mfma_f32_16x16x32_bf16 v[92:95], v[162:165], v[226:229], v[92:95]
	v_mfma_f32_16x16x32_bf16 v[96:99], v[214:217], v[226:229], v[96:99]
	v_mfma_f32_16x16x32_bf16 v[36:39], v[218:221], v[226:229], v[36:39]
	ds_read_b128 v[226:229], v6 offset:15360
	s_waitcnt lgkmcnt(3)
	v_mfma_f32_16x16x32_bf16 v[104:107], v[158:161], v[166:169], v[104:107]
	v_mfma_f32_16x16x32_bf16 v[108:111], v[162:165], v[166:169], v[108:111]
	v_mfma_f32_16x16x32_bf16 v[112:115], v[214:217], v[166:169], v[112:115]
	v_mfma_f32_16x16x32_bf16 v[52:55], v[218:221], v[166:169], v[52:55]
	s_waitcnt lgkmcnt(2)
	v_mfma_f32_16x16x32_bf16 v[116:119], v[158:161], v[178:181], v[116:119]
	v_mfma_f32_16x16x32_bf16 v[120:123], v[162:165], v[178:181], v[120:123]
	v_mfma_f32_16x16x32_bf16 v[124:127], v[214:217], v[178:181], v[124:127]
	v_mfma_f32_16x16x32_bf16 v[68:71], v[218:221], v[178:181], v[68:71]
	s_waitcnt lgkmcnt(1)
	v_mfma_f32_16x16x32_bf16 v[128:131], v[158:161], v[222:225], v[128:131]
	v_mfma_f32_16x16x32_bf16 v[132:135], v[162:165], v[222:225], v[132:135]
	v_mfma_f32_16x16x32_bf16 v[136:139], v[214:217], v[222:225], v[136:139]
	v_mfma_f32_16x16x32_bf16 v[84:87], v[218:221], v[222:225], v[84:87]
	s_waitcnt lgkmcnt(0)
	v_mfma_f32_16x16x32_bf16 v[100:103], v[158:161], v[226:229], v[100:103]
	v_mfma_f32_16x16x32_bf16 v[140:143], v[162:165], v[226:229], v[140:143]
	v_mfma_f32_16x16x32_bf16 v[150:153], v[214:217], v[226:229], v[150:153]
	v_mfma_f32_16x16x32_bf16 v[154:157], v[218:221], v[226:229], v[154:157]
	s_add_u32 s46, s0, 0x1500
	s_addc_u32 s47, s1, 0
	s_add_u32 s48, s14, 0x1500
	s_waitcnt vmcnt(0)
	s_barrier
	s_addc_u32 s49, s15, 0
	ds_read_b128 v[158:161], v8
	ds_read_b128 v[162:165], v12
	ds_read_b128 v[166:169], v9
	ds_read_b128 v[178:181], v13
	ds_read_b128 v[214:217], v11
	ds_read_b128 v[218:221], v10
	ds_read_b128 v[222:225], v14
	ds_read_b128 v[226:229], v15
	s_waitcnt lgkmcnt(6)
	v_mfma_f32_16x16x32_bf16 v[40:43], v[158:161], v[162:165], v[40:43]
	s_waitcnt lgkmcnt(5)
	v_mfma_f32_16x16x32_bf16 v[44:47], v[166:169], v[162:165], v[44:47]
	s_waitcnt lgkmcnt(4)
	v_mfma_f32_16x16x32_bf16 v[56:59], v[158:161], v[178:181], v[56:59]
	s_mov_b32 m0, s27
	v_mfma_f32_16x16x32_bf16 v[60:63], v[166:169], v[178:181], v[60:63]
	global_load_lds_dwordx4 v0, s[46:47]
	s_waitcnt lgkmcnt(3)
	v_mfma_f32_16x16x32_bf16 v[48:51], v[214:217], v[162:165], v[48:51]
	v_mfma_f32_16x16x32_bf16 v[64:67], v[214:217], v[178:181], v[64:67]
	s_waitcnt lgkmcnt(2)
	v_mfma_f32_16x16x32_bf16 v[174:177], v[218:221], v[162:165], v[174:177]
	ds_read_b128 v[162:165], v16
	v_mfma_f32_16x16x32_bf16 v[170:173], v[218:221], v[178:181], v[170:173]
	ds_read_b128 v[178:181], v17
	s_waitcnt lgkmcnt(3)
	s_mov_b32 m0, s28
	v_mfma_f32_16x16x32_bf16 v[72:75], v[158:161], v[222:225], v[72:75]
	global_load_lds_dwordx4 v0, s[48:49]
	v_mfma_f32_16x16x32_bf16 v[76:79], v[166:169], v[222:225], v[76:79]
	v_mfma_f32_16x16x32_bf16 v[80:83], v[214:217], v[222:225], v[80:83]
	v_mfma_f32_16x16x32_bf16 v[32:35], v[218:221], v[222:225], v[32:35]
	ds_read_b128 v[222:225], v18
	s_waitcnt lgkmcnt(3)
	v_mfma_f32_16x16x32_bf16 v[88:91], v[158:161], v[226:229], v[88:91]
	s_mov_b32 m0, s29
	v_mfma_f32_16x16x32_bf16 v[92:95], v[166:169], v[226:229], v[92:95]
	global_load_lds_dwordx4 v2, s[46:47]
	v_mfma_f32_16x16x32_bf16 v[96:99], v[214:217], v[226:229], v[96:99]
	v_mfma_f32_16x16x32_bf16 v[36:39], v[218:221], v[226:229], v[36:39]
	ds_read_b128 v[226:229], v19
	s_waitcnt lgkmcnt(3)
	v_mfma_f32_16x16x32_bf16 v[104:107], v[158:161], v[162:165], v[104:107]
	s_waitcnt lgkmcnt(2)
	v_mfma_f32_16x16x32_bf16 v[116:119], v[158:161], v[178:181], v[116:119]
	s_waitcnt lgkmcnt(1)
	s_mov_b32 m0, s30
	v_mfma_f32_16x16x32_bf16 v[128:131], v[158:161], v[222:225], v[128:131]
	global_load_lds_dwordx4 v2, s[48:49]
	s_waitcnt lgkmcnt(0)
	v_mfma_f32_16x16x32_bf16 v[100:103], v[158:161], v[226:229], v[100:103]
	ds_read_b128 v[158:161], v20
	v_mfma_f32_16x16x32_bf16 v[108:111], v[166:169], v[162:165], v[108:111]
	v_mfma_f32_16x16x32_bf16 v[120:123], v[166:169], v[178:181], v[120:123]
	v_mfma_f32_16x16x32_bf16 v[132:135], v[166:169], v[222:225], v[132:135]
	s_mov_b32 m0, s31
	v_mfma_f32_16x16x32_bf16 v[140:143], v[166:169], v[226:229], v[140:143]
	global_load_lds_dwordx4 v4, s[46:47]
	ds_read_b128 v[166:169], v24
	v_mfma_f32_16x16x32_bf16 v[112:115], v[214:217], v[162:165], v[112:115]
	v_mfma_f32_16x16x32_bf16 v[52:55], v[218:221], v[162:165], v[52:55]
	ds_read_b128 v[162:165], v21
	v_mfma_f32_16x16x32_bf16 v[124:127], v[214:217], v[178:181], v[124:127]
	v_mfma_f32_16x16x32_bf16 v[68:71], v[218:221], v[178:181], v[68:71]
	ds_read_b128 v[178:181], v25
	s_mov_b32 m0, s34
	v_mfma_f32_16x16x32_bf16 v[136:139], v[214:217], v[222:225], v[136:139]
	global_load_lds_dwordx4 v4, s[48:49]
	v_mfma_f32_16x16x32_bf16 v[84:87], v[218:221], v[222:225], v[84:87]
	ds_read_b128 v[222:225], v26
	v_mfma_f32_16x16x32_bf16 v[150:153], v[214:217], v[226:229], v[150:153]
	ds_read_b128 v[214:217], v23
	v_mfma_f32_16x16x32_bf16 v[154:157], v[218:221], v[226:229], v[154:157]
	ds_read_b128 v[218:221], v22
	ds_read_b128 v[226:229], v27
	s_waitcnt lgkmcnt(6)
	v_mfma_f32_16x16x32_bf16 v[40:43], v[158:161], v[166:169], v[40:43]
	s_waitcnt lgkmcnt(5)
	s_mov_b32 m0, s35
	v_mfma_f32_16x16x32_bf16 v[44:47], v[162:165], v[166:169], v[44:47]
	global_load_lds_dwordx4 v146, s[46:47]
	s_waitcnt lgkmcnt(4)
	v_mfma_f32_16x16x32_bf16 v[56:59], v[158:161], v[178:181], v[56:59]
	v_mfma_f32_16x16x32_bf16 v[60:63], v[162:165], v[178:181], v[60:63]
	s_waitcnt lgkmcnt(3)
	v_mfma_f32_16x16x32_bf16 v[72:75], v[158:161], v[222:225], v[72:75]
	v_mfma_f32_16x16x32_bf16 v[76:79], v[162:165], v[222:225], v[76:79]
	s_waitcnt lgkmcnt(2)
	s_mov_b32 m0, s36
	v_mfma_f32_16x16x32_bf16 v[48:51], v[214:217], v[166:169], v[48:51]
	global_load_lds_dwordx4 v146, s[48:49]
	s_waitcnt lgkmcnt(1)
	v_mfma_f32_16x16x32_bf16 v[174:177], v[218:221], v[166:169], v[174:177]
	ds_read_b128 v[166:169], v28
	v_mfma_f32_16x16x32_bf16 v[64:67], v[214:217], v[178:181], v[64:67]
	v_mfma_f32_16x16x32_bf16 v[170:173], v[218:221], v[178:181], v[170:173]
	ds_read_b128 v[178:181], v29
	v_mfma_f32_16x16x32_bf16 v[80:83], v[214:217], v[222:225], v[80:83]
	v_mfma_f32_16x16x32_bf16 v[32:35], v[218:221], v[222:225], v[32:35]
	ds_read_b128 v[222:225], v30
	s_waitcnt lgkmcnt(3)
	v_mfma_f32_16x16x32_bf16 v[88:91], v[158:161], v[226:229], v[88:91]
	v_mfma_f32_16x16x32_bf16 v[92:95], v[162:165], v[226:229], v[92:95]
	v_mfma_f32_16x16x32_bf16 v[96:99], v[214:217], v[226:229], v[96:99]
	v_mfma_f32_16x16x32_bf16 v[36:39], v[218:221], v[226:229], v[36:39]
	ds_read_b128 v[226:229], v31
	s_waitcnt lgkmcnt(3)
	v_mfma_f32_16x16x32_bf16 v[104:107], v[158:161], v[166:169], v[104:107]
	v_mfma_f32_16x16x32_bf16 v[108:111], v[162:165], v[166:169], v[108:111]
	v_mfma_f32_16x16x32_bf16 v[112:115], v[214:217], v[166:169], v[112:115]
	v_mfma_f32_16x16x32_bf16 v[52:55], v[218:221], v[166:169], v[52:55]
	s_waitcnt lgkmcnt(2)
	v_mfma_f32_16x16x32_bf16 v[116:119], v[158:161], v[178:181], v[116:119]
	v_mfma_f32_16x16x32_bf16 v[120:123], v[162:165], v[178:181], v[120:123]
	v_mfma_f32_16x16x32_bf16 v[124:127], v[214:217], v[178:181], v[124:127]
	v_mfma_f32_16x16x32_bf16 v[68:71], v[218:221], v[178:181], v[68:71]
	s_waitcnt lgkmcnt(1)
	v_mfma_f32_16x16x32_bf16 v[128:131], v[158:161], v[222:225], v[128:131]
	v_mfma_f32_16x16x32_bf16 v[132:135], v[162:165], v[222:225], v[132:135]
	v_mfma_f32_16x16x32_bf16 v[136:139], v[214:217], v[222:225], v[136:139]
	v_mfma_f32_16x16x32_bf16 v[84:87], v[218:221], v[222:225], v[84:87]
	s_waitcnt lgkmcnt(0)
	v_mfma_f32_16x16x32_bf16 v[100:103], v[158:161], v[226:229], v[100:103]
	v_mfma_f32_16x16x32_bf16 v[140:143], v[162:165], v[226:229], v[140:143]
	v_mfma_f32_16x16x32_bf16 v[150:153], v[214:217], v[226:229], v[150:153]
	v_mfma_f32_16x16x32_bf16 v[154:157], v[218:221], v[226:229], v[154:157]
	s_add_u32 s46, s0, 0x1580
	s_addc_u32 s47, s1, 0
	s_add_u32 s48, s14, 0x1580
	s_waitcnt vmcnt(0)
	s_barrier
	s_addc_u32 s49, s15, 0
	ds_read_b128 v[158:161], v7 offset:32768
	ds_read_b128 v[162:165], v6
	ds_read_b128 v[166:169], v7 offset:34816
	ds_read_b128 v[178:181], v6 offset:2048
	ds_read_b128 v[214:217], v7 offset:36864
	ds_read_b128 v[218:221], v7 offset:38912
	ds_read_b128 v[222:225], v6 offset:4096
	ds_read_b128 v[226:229], v6 offset:6144
	s_waitcnt lgkmcnt(6)
	v_mfma_f32_16x16x32_bf16 v[40:43], v[158:161], v[162:165], v[40:43]
	s_waitcnt lgkmcnt(5)
	v_mfma_f32_16x16x32_bf16 v[44:47], v[166:169], v[162:165], v[44:47]
	s_waitcnt lgkmcnt(4)
	v_mfma_f32_16x16x32_bf16 v[56:59], v[158:161], v[178:181], v[56:59]
	s_mov_b32 m0, s38
	v_mfma_f32_16x16x32_bf16 v[60:63], v[166:169], v[178:181], v[60:63]
	global_load_lds_dwordx4 v0, s[46:47]
	s_waitcnt lgkmcnt(3)
	v_mfma_f32_16x16x32_bf16 v[48:51], v[214:217], v[162:165], v[48:51]
	v_mfma_f32_16x16x32_bf16 v[64:67], v[214:217], v[178:181], v[64:67]
	s_waitcnt lgkmcnt(2)
	v_mfma_f32_16x16x32_bf16 v[174:177], v[218:221], v[162:165], v[174:177]
	ds_read_b128 v[162:165], v6 offset:8192
	v_mfma_f32_16x16x32_bf16 v[170:173], v[218:221], v[178:181], v[170:173]
	ds_read_b128 v[178:181], v6 offset:10240
	s_waitcnt lgkmcnt(3)
	s_mov_b32 m0, s37
	v_mfma_f32_16x16x32_bf16 v[72:75], v[158:161], v[222:225], v[72:75]
	global_load_lds_dwordx4 v0, s[48:49]
	v_mfma_f32_16x16x32_bf16 v[76:79], v[166:169], v[222:225], v[76:79]
	v_mfma_f32_16x16x32_bf16 v[80:83], v[214:217], v[222:225], v[80:83]
	v_mfma_f32_16x16x32_bf16 v[32:35], v[218:221], v[222:225], v[32:35]
	ds_read_b128 v[222:225], v6 offset:12288
	s_waitcnt lgkmcnt(3)
	v_mfma_f32_16x16x32_bf16 v[88:91], v[158:161], v[226:229], v[88:91]
	s_mov_b32 m0, s39
	v_mfma_f32_16x16x32_bf16 v[92:95], v[166:169], v[226:229], v[92:95]
	global_load_lds_dwordx4 v2, s[46:47]
	v_mfma_f32_16x16x32_bf16 v[96:99], v[214:217], v[226:229], v[96:99]
	v_mfma_f32_16x16x32_bf16 v[36:39], v[218:221], v[226:229], v[36:39]
	ds_read_b128 v[226:229], v6 offset:14336
	s_waitcnt lgkmcnt(3)
	v_mfma_f32_16x16x32_bf16 v[104:107], v[158:161], v[162:165], v[104:107]
	s_waitcnt lgkmcnt(2)
	v_mfma_f32_16x16x32_bf16 v[116:119], v[158:161], v[178:181], v[116:119]
	s_waitcnt lgkmcnt(1)
	s_mov_b32 m0, s40
	v_mfma_f32_16x16x32_bf16 v[128:131], v[158:161], v[222:225], v[128:131]
	global_load_lds_dwordx4 v2, s[48:49]
	s_waitcnt lgkmcnt(0)
	v_mfma_f32_16x16x32_bf16 v[100:103], v[158:161], v[226:229], v[100:103]
	ds_read_b128 v[158:161], v7 offset:33792
	v_mfma_f32_16x16x32_bf16 v[108:111], v[166:169], v[162:165], v[108:111]
	v_mfma_f32_16x16x32_bf16 v[120:123], v[166:169], v[178:181], v[120:123]
	v_mfma_f32_16x16x32_bf16 v[132:135], v[166:169], v[222:225], v[132:135]
	s_mov_b32 m0, s41
	v_mfma_f32_16x16x32_bf16 v[140:143], v[166:169], v[226:229], v[140:143]
	global_load_lds_dwordx4 v4, s[46:47]
	ds_read_b128 v[166:169], v6 offset:1024
	v_mfma_f32_16x16x32_bf16 v[112:115], v[214:217], v[162:165], v[112:115]
	v_mfma_f32_16x16x32_bf16 v[52:55], v[218:221], v[162:165], v[52:55]
	ds_read_b128 v[162:165], v7 offset:35840
	v_mfma_f32_16x16x32_bf16 v[124:127], v[214:217], v[178:181], v[124:127]
	v_mfma_f32_16x16x32_bf16 v[68:71], v[218:221], v[178:181], v[68:71]
	ds_read_b128 v[178:181], v6 offset:3072
	s_mov_b32 m0, s42
	v_mfma_f32_16x16x32_bf16 v[136:139], v[214:217], v[222:225], v[136:139]
	global_load_lds_dwordx4 v4, s[48:49]
	v_mfma_f32_16x16x32_bf16 v[84:87], v[218:221], v[222:225], v[84:87]
	ds_read_b128 v[222:225], v6 offset:5120
	v_mfma_f32_16x16x32_bf16 v[150:153], v[214:217], v[226:229], v[150:153]
	ds_read_b128 v[214:217], v7 offset:37888
	v_mfma_f32_16x16x32_bf16 v[154:157], v[218:221], v[226:229], v[154:157]
	ds_read_b128 v[218:221], v7 offset:39936
	ds_read_b128 v[226:229], v6 offset:7168
	s_waitcnt lgkmcnt(6)
	v_mfma_f32_16x16x32_bf16 v[40:43], v[158:161], v[166:169], v[40:43]
	s_waitcnt lgkmcnt(5)
	s_mov_b32 m0, s43
	v_mfma_f32_16x16x32_bf16 v[44:47], v[162:165], v[166:169], v[44:47]
	global_load_lds_dwordx4 v146, s[46:47]
	s_waitcnt lgkmcnt(4)
	v_mfma_f32_16x16x32_bf16 v[56:59], v[158:161], v[178:181], v[56:59]
	v_mfma_f32_16x16x32_bf16 v[60:63], v[162:165], v[178:181], v[60:63]
	s_waitcnt lgkmcnt(3)
	v_mfma_f32_16x16x32_bf16 v[72:75], v[158:161], v[222:225], v[72:75]
	v_mfma_f32_16x16x32_bf16 v[76:79], v[162:165], v[222:225], v[76:79]
	s_waitcnt lgkmcnt(2)
	s_mov_b32 m0, s44
	v_mfma_f32_16x16x32_bf16 v[48:51], v[214:217], v[166:169], v[48:51]
	global_load_lds_dwordx4 v146, s[48:49]
	s_waitcnt lgkmcnt(1)
	v_mfma_f32_16x16x32_bf16 v[174:177], v[218:221], v[166:169], v[174:177]
	ds_read_b128 v[166:169], v6 offset:9216
	v_mfma_f32_16x16x32_bf16 v[64:67], v[214:217], v[178:181], v[64:67]
	v_mfma_f32_16x16x32_bf16 v[170:173], v[218:221], v[178:181], v[170:173]
	ds_read_b128 v[178:181], v6 offset:11264
	v_mfma_f32_16x16x32_bf16 v[80:83], v[214:217], v[222:225], v[80:83]
	v_mfma_f32_16x16x32_bf16 v[32:35], v[218:221], v[222:225], v[32:35]
	ds_read_b128 v[222:225], v6 offset:13312
	s_waitcnt lgkmcnt(3)
	v_mfma_f32_16x16x32_bf16 v[88:91], v[158:161], v[226:229], v[88:91]
	v_mfma_f32_16x16x32_bf16 v[92:95], v[162:165], v[226:229], v[92:95]
	v_mfma_f32_16x16x32_bf16 v[96:99], v[214:217], v[226:229], v[96:99]
	v_mfma_f32_16x16x32_bf16 v[36:39], v[218:221], v[226:229], v[36:39]
	ds_read_b128 v[226:229], v6 offset:15360
	s_waitcnt lgkmcnt(3)
	v_mfma_f32_16x16x32_bf16 v[104:107], v[158:161], v[166:169], v[104:107]
	v_mfma_f32_16x16x32_bf16 v[108:111], v[162:165], v[166:169], v[108:111]
	v_mfma_f32_16x16x32_bf16 v[112:115], v[214:217], v[166:169], v[112:115]
	v_mfma_f32_16x16x32_bf16 v[52:55], v[218:221], v[166:169], v[52:55]
	s_waitcnt lgkmcnt(2)
	v_mfma_f32_16x16x32_bf16 v[116:119], v[158:161], v[178:181], v[116:119]
	v_mfma_f32_16x16x32_bf16 v[120:123], v[162:165], v[178:181], v[120:123]
	v_mfma_f32_16x16x32_bf16 v[124:127], v[214:217], v[178:181], v[124:127]
	v_mfma_f32_16x16x32_bf16 v[68:71], v[218:221], v[178:181], v[68:71]
	s_waitcnt lgkmcnt(1)
	v_mfma_f32_16x16x32_bf16 v[128:131], v[158:161], v[222:225], v[128:131]
	v_mfma_f32_16x16x32_bf16 v[132:135], v[162:165], v[222:225], v[132:135]
	v_mfma_f32_16x16x32_bf16 v[136:139], v[214:217], v[222:225], v[136:139]
	v_mfma_f32_16x16x32_bf16 v[84:87], v[218:221], v[222:225], v[84:87]
	s_waitcnt lgkmcnt(0)
	v_mfma_f32_16x16x32_bf16 v[100:103], v[158:161], v[226:229], v[100:103]
	v_mfma_f32_16x16x32_bf16 v[140:143], v[162:165], v[226:229], v[140:143]
	v_mfma_f32_16x16x32_bf16 v[150:153], v[214:217], v[226:229], v[150:153]
	v_mfma_f32_16x16x32_bf16 v[154:157], v[218:221], v[226:229], v[154:157]
	s_add_u32 s46, s0, 0x1600
	s_addc_u32 s47, s1, 0
	s_add_u32 s48, s14, 0x1600
	s_waitcnt vmcnt(0)
	s_barrier
	s_addc_u32 s49, s15, 0
	ds_read_b128 v[158:161], v8
	ds_read_b128 v[162:165], v12
	ds_read_b128 v[166:169], v9
	ds_read_b128 v[178:181], v13
	ds_read_b128 v[214:217], v11
	ds_read_b128 v[218:221], v10
	ds_read_b128 v[222:225], v14
	ds_read_b128 v[226:229], v15
	s_waitcnt lgkmcnt(6)
	v_mfma_f32_16x16x32_bf16 v[40:43], v[158:161], v[162:165], v[40:43]
	s_waitcnt lgkmcnt(5)
	v_mfma_f32_16x16x32_bf16 v[44:47], v[166:169], v[162:165], v[44:47]
	s_waitcnt lgkmcnt(4)
	v_mfma_f32_16x16x32_bf16 v[56:59], v[158:161], v[178:181], v[56:59]
	s_mov_b32 m0, s27
	v_mfma_f32_16x16x32_bf16 v[60:63], v[166:169], v[178:181], v[60:63]
	global_load_lds_dwordx4 v0, s[46:47]
	s_waitcnt lgkmcnt(3)
	v_mfma_f32_16x16x32_bf16 v[48:51], v[214:217], v[162:165], v[48:51]
	v_mfma_f32_16x16x32_bf16 v[64:67], v[214:217], v[178:181], v[64:67]
	s_waitcnt lgkmcnt(2)
	v_mfma_f32_16x16x32_bf16 v[174:177], v[218:221], v[162:165], v[174:177]
	ds_read_b128 v[162:165], v16
	v_mfma_f32_16x16x32_bf16 v[170:173], v[218:221], v[178:181], v[170:173]
	ds_read_b128 v[178:181], v17
	s_waitcnt lgkmcnt(3)
	s_mov_b32 m0, s28
	v_mfma_f32_16x16x32_bf16 v[72:75], v[158:161], v[222:225], v[72:75]
	global_load_lds_dwordx4 v0, s[48:49]
	v_mfma_f32_16x16x32_bf16 v[76:79], v[166:169], v[222:225], v[76:79]
	v_mfma_f32_16x16x32_bf16 v[80:83], v[214:217], v[222:225], v[80:83]
	v_mfma_f32_16x16x32_bf16 v[32:35], v[218:221], v[222:225], v[32:35]
	ds_read_b128 v[222:225], v18
	s_waitcnt lgkmcnt(3)
	v_mfma_f32_16x16x32_bf16 v[88:91], v[158:161], v[226:229], v[88:91]
	s_mov_b32 m0, s29
	v_mfma_f32_16x16x32_bf16 v[92:95], v[166:169], v[226:229], v[92:95]
	global_load_lds_dwordx4 v2, s[46:47]
	v_mfma_f32_16x16x32_bf16 v[96:99], v[214:217], v[226:229], v[96:99]
	v_mfma_f32_16x16x32_bf16 v[36:39], v[218:221], v[226:229], v[36:39]
	ds_read_b128 v[226:229], v19
	s_waitcnt lgkmcnt(3)
	v_mfma_f32_16x16x32_bf16 v[104:107], v[158:161], v[162:165], v[104:107]
	s_waitcnt lgkmcnt(2)
	v_mfma_f32_16x16x32_bf16 v[116:119], v[158:161], v[178:181], v[116:119]
	s_waitcnt lgkmcnt(1)
	s_mov_b32 m0, s30
	v_mfma_f32_16x16x32_bf16 v[128:131], v[158:161], v[222:225], v[128:131]
	global_load_lds_dwordx4 v2, s[48:49]
	s_waitcnt lgkmcnt(0)
	v_mfma_f32_16x16x32_bf16 v[100:103], v[158:161], v[226:229], v[100:103]
	ds_read_b128 v[158:161], v20
	v_mfma_f32_16x16x32_bf16 v[108:111], v[166:169], v[162:165], v[108:111]
	v_mfma_f32_16x16x32_bf16 v[120:123], v[166:169], v[178:181], v[120:123]
	v_mfma_f32_16x16x32_bf16 v[132:135], v[166:169], v[222:225], v[132:135]
	s_mov_b32 m0, s31
	v_mfma_f32_16x16x32_bf16 v[140:143], v[166:169], v[226:229], v[140:143]
	global_load_lds_dwordx4 v4, s[46:47]
	ds_read_b128 v[166:169], v24
	v_mfma_f32_16x16x32_bf16 v[112:115], v[214:217], v[162:165], v[112:115]
	v_mfma_f32_16x16x32_bf16 v[52:55], v[218:221], v[162:165], v[52:55]
	ds_read_b128 v[162:165], v21
	v_mfma_f32_16x16x32_bf16 v[124:127], v[214:217], v[178:181], v[124:127]
	v_mfma_f32_16x16x32_bf16 v[68:71], v[218:221], v[178:181], v[68:71]
	ds_read_b128 v[178:181], v25
	s_mov_b32 m0, s34
	v_mfma_f32_16x16x32_bf16 v[136:139], v[214:217], v[222:225], v[136:139]
	global_load_lds_dwordx4 v4, s[48:49]
	v_mfma_f32_16x16x32_bf16 v[84:87], v[218:221], v[222:225], v[84:87]
	ds_read_b128 v[222:225], v26
	v_mfma_f32_16x16x32_bf16 v[150:153], v[214:217], v[226:229], v[150:153]
	ds_read_b128 v[214:217], v23
	v_mfma_f32_16x16x32_bf16 v[154:157], v[218:221], v[226:229], v[154:157]
	ds_read_b128 v[218:221], v22
	ds_read_b128 v[226:229], v27
	s_waitcnt lgkmcnt(6)
	v_mfma_f32_16x16x32_bf16 v[40:43], v[158:161], v[166:169], v[40:43]
	s_waitcnt lgkmcnt(5)
	s_mov_b32 m0, s35
	v_mfma_f32_16x16x32_bf16 v[44:47], v[162:165], v[166:169], v[44:47]
	global_load_lds_dwordx4 v146, s[46:47]
	s_waitcnt lgkmcnt(4)
	v_mfma_f32_16x16x32_bf16 v[56:59], v[158:161], v[178:181], v[56:59]
	v_mfma_f32_16x16x32_bf16 v[60:63], v[162:165], v[178:181], v[60:63]
	s_waitcnt lgkmcnt(3)
	v_mfma_f32_16x16x32_bf16 v[72:75], v[158:161], v[222:225], v[72:75]
	v_mfma_f32_16x16x32_bf16 v[76:79], v[162:165], v[222:225], v[76:79]
	s_waitcnt lgkmcnt(2)
	s_mov_b32 m0, s36
	v_mfma_f32_16x16x32_bf16 v[48:51], v[214:217], v[166:169], v[48:51]
	global_load_lds_dwordx4 v146, s[48:49]
	s_waitcnt lgkmcnt(1)
	v_mfma_f32_16x16x32_bf16 v[174:177], v[218:221], v[166:169], v[174:177]
	ds_read_b128 v[166:169], v28
	v_mfma_f32_16x16x32_bf16 v[64:67], v[214:217], v[178:181], v[64:67]
	v_mfma_f32_16x16x32_bf16 v[170:173], v[218:221], v[178:181], v[170:173]
	ds_read_b128 v[178:181], v29
	v_mfma_f32_16x16x32_bf16 v[80:83], v[214:217], v[222:225], v[80:83]
	v_mfma_f32_16x16x32_bf16 v[32:35], v[218:221], v[222:225], v[32:35]
	ds_read_b128 v[222:225], v30
	s_waitcnt lgkmcnt(3)
	v_mfma_f32_16x16x32_bf16 v[88:91], v[158:161], v[226:229], v[88:91]
	v_mfma_f32_16x16x32_bf16 v[92:95], v[162:165], v[226:229], v[92:95]
	v_mfma_f32_16x16x32_bf16 v[96:99], v[214:217], v[226:229], v[96:99]
	v_mfma_f32_16x16x32_bf16 v[36:39], v[218:221], v[226:229], v[36:39]
	ds_read_b128 v[226:229], v31
	s_waitcnt lgkmcnt(3)
	v_mfma_f32_16x16x32_bf16 v[104:107], v[158:161], v[166:169], v[104:107]
	v_mfma_f32_16x16x32_bf16 v[108:111], v[162:165], v[166:169], v[108:111]
	v_mfma_f32_16x16x32_bf16 v[112:115], v[214:217], v[166:169], v[112:115]
	v_mfma_f32_16x16x32_bf16 v[52:55], v[218:221], v[166:169], v[52:55]
	s_waitcnt lgkmcnt(2)
	v_mfma_f32_16x16x32_bf16 v[116:119], v[158:161], v[178:181], v[116:119]
	v_mfma_f32_16x16x32_bf16 v[120:123], v[162:165], v[178:181], v[120:123]
	v_mfma_f32_16x16x32_bf16 v[124:127], v[214:217], v[178:181], v[124:127]
	v_mfma_f32_16x16x32_bf16 v[68:71], v[218:221], v[178:181], v[68:71]
	s_waitcnt lgkmcnt(1)
	v_mfma_f32_16x16x32_bf16 v[128:131], v[158:161], v[222:225], v[128:131]
	v_mfma_f32_16x16x32_bf16 v[132:135], v[162:165], v[222:225], v[132:135]
	v_mfma_f32_16x16x32_bf16 v[136:139], v[214:217], v[222:225], v[136:139]
	v_mfma_f32_16x16x32_bf16 v[84:87], v[218:221], v[222:225], v[84:87]
	s_waitcnt lgkmcnt(0)
	v_mfma_f32_16x16x32_bf16 v[100:103], v[158:161], v[226:229], v[100:103]
	v_mfma_f32_16x16x32_bf16 v[140:143], v[162:165], v[226:229], v[140:143]
	v_mfma_f32_16x16x32_bf16 v[150:153], v[214:217], v[226:229], v[150:153]
	v_mfma_f32_16x16x32_bf16 v[154:157], v[218:221], v[226:229], v[154:157]
	s_add_u32 s46, s0, 0x1680
	s_addc_u32 s47, s1, 0
	s_add_u32 s48, s14, 0x1680
	s_waitcnt vmcnt(0)
	s_barrier
	s_addc_u32 s49, s15, 0
	ds_read_b128 v[158:161], v7 offset:32768
	ds_read_b128 v[162:165], v6
	ds_read_b128 v[166:169], v7 offset:34816
	ds_read_b128 v[178:181], v6 offset:2048
	ds_read_b128 v[214:217], v7 offset:36864
	ds_read_b128 v[218:221], v7 offset:38912
	ds_read_b128 v[222:225], v6 offset:4096
	ds_read_b128 v[226:229], v6 offset:6144
	s_waitcnt lgkmcnt(6)
	v_mfma_f32_16x16x32_bf16 v[40:43], v[158:161], v[162:165], v[40:43]
	s_waitcnt lgkmcnt(5)
	v_mfma_f32_16x16x32_bf16 v[44:47], v[166:169], v[162:165], v[44:47]
	s_waitcnt lgkmcnt(4)
	v_mfma_f32_16x16x32_bf16 v[56:59], v[158:161], v[178:181], v[56:59]
	s_mov_b32 m0, s38
	v_mfma_f32_16x16x32_bf16 v[60:63], v[166:169], v[178:181], v[60:63]
	global_load_lds_dwordx4 v0, s[46:47]
	s_waitcnt lgkmcnt(3)
	v_mfma_f32_16x16x32_bf16 v[48:51], v[214:217], v[162:165], v[48:51]
	v_mfma_f32_16x16x32_bf16 v[64:67], v[214:217], v[178:181], v[64:67]
	s_waitcnt lgkmcnt(2)
	v_mfma_f32_16x16x32_bf16 v[174:177], v[218:221], v[162:165], v[174:177]
	ds_read_b128 v[162:165], v6 offset:8192
	v_mfma_f32_16x16x32_bf16 v[170:173], v[218:221], v[178:181], v[170:173]
	ds_read_b128 v[178:181], v6 offset:10240
	s_waitcnt lgkmcnt(3)
	s_mov_b32 m0, s37
	v_mfma_f32_16x16x32_bf16 v[72:75], v[158:161], v[222:225], v[72:75]
	global_load_lds_dwordx4 v0, s[48:49]
	v_mfma_f32_16x16x32_bf16 v[76:79], v[166:169], v[222:225], v[76:79]
	v_mfma_f32_16x16x32_bf16 v[80:83], v[214:217], v[222:225], v[80:83]
	v_mfma_f32_16x16x32_bf16 v[32:35], v[218:221], v[222:225], v[32:35]
	ds_read_b128 v[222:225], v6 offset:12288
	s_waitcnt lgkmcnt(3)
	v_mfma_f32_16x16x32_bf16 v[88:91], v[158:161], v[226:229], v[88:91]
	s_mov_b32 m0, s39
	v_mfma_f32_16x16x32_bf16 v[92:95], v[166:169], v[226:229], v[92:95]
	global_load_lds_dwordx4 v2, s[46:47]
	v_mfma_f32_16x16x32_bf16 v[96:99], v[214:217], v[226:229], v[96:99]
	v_mfma_f32_16x16x32_bf16 v[36:39], v[218:221], v[226:229], v[36:39]
	ds_read_b128 v[226:229], v6 offset:14336
	s_waitcnt lgkmcnt(3)
	v_mfma_f32_16x16x32_bf16 v[104:107], v[158:161], v[162:165], v[104:107]
	s_waitcnt lgkmcnt(2)
	v_mfma_f32_16x16x32_bf16 v[116:119], v[158:161], v[178:181], v[116:119]
	s_waitcnt lgkmcnt(1)
	s_mov_b32 m0, s40
	v_mfma_f32_16x16x32_bf16 v[128:131], v[158:161], v[222:225], v[128:131]
	global_load_lds_dwordx4 v2, s[48:49]
	s_waitcnt lgkmcnt(0)
	v_mfma_f32_16x16x32_bf16 v[100:103], v[158:161], v[226:229], v[100:103]
	ds_read_b128 v[158:161], v7 offset:33792
	v_mfma_f32_16x16x32_bf16 v[108:111], v[166:169], v[162:165], v[108:111]
	v_mfma_f32_16x16x32_bf16 v[120:123], v[166:169], v[178:181], v[120:123]
	v_mfma_f32_16x16x32_bf16 v[132:135], v[166:169], v[222:225], v[132:135]
	s_mov_b32 m0, s41
	v_mfma_f32_16x16x32_bf16 v[140:143], v[166:169], v[226:229], v[140:143]
	global_load_lds_dwordx4 v4, s[46:47]
	ds_read_b128 v[166:169], v6 offset:1024
	v_mfma_f32_16x16x32_bf16 v[112:115], v[214:217], v[162:165], v[112:115]
	v_mfma_f32_16x16x32_bf16 v[52:55], v[218:221], v[162:165], v[52:55]
	ds_read_b128 v[162:165], v7 offset:35840
	v_mfma_f32_16x16x32_bf16 v[124:127], v[214:217], v[178:181], v[124:127]
	v_mfma_f32_16x16x32_bf16 v[68:71], v[218:221], v[178:181], v[68:71]
	ds_read_b128 v[178:181], v6 offset:3072
	s_mov_b32 m0, s42
	v_mfma_f32_16x16x32_bf16 v[136:139], v[214:217], v[222:225], v[136:139]
	global_load_lds_dwordx4 v4, s[48:49]
	v_mfma_f32_16x16x32_bf16 v[84:87], v[218:221], v[222:225], v[84:87]
	ds_read_b128 v[222:225], v6 offset:5120
	v_mfma_f32_16x16x32_bf16 v[150:153], v[214:217], v[226:229], v[150:153]
	ds_read_b128 v[214:217], v7 offset:37888
	v_mfma_f32_16x16x32_bf16 v[154:157], v[218:221], v[226:229], v[154:157]
	ds_read_b128 v[218:221], v7 offset:39936
	ds_read_b128 v[226:229], v6 offset:7168
	s_waitcnt lgkmcnt(6)
	v_mfma_f32_16x16x32_bf16 v[40:43], v[158:161], v[166:169], v[40:43]
	s_waitcnt lgkmcnt(5)
	s_mov_b32 m0, s43
	v_mfma_f32_16x16x32_bf16 v[44:47], v[162:165], v[166:169], v[44:47]
	global_load_lds_dwordx4 v146, s[46:47]
	s_waitcnt lgkmcnt(4)
	v_mfma_f32_16x16x32_bf16 v[56:59], v[158:161], v[178:181], v[56:59]
	v_mfma_f32_16x16x32_bf16 v[60:63], v[162:165], v[178:181], v[60:63]
	s_waitcnt lgkmcnt(3)
	v_mfma_f32_16x16x32_bf16 v[72:75], v[158:161], v[222:225], v[72:75]
	v_mfma_f32_16x16x32_bf16 v[76:79], v[162:165], v[222:225], v[76:79]
	s_waitcnt lgkmcnt(2)
	s_mov_b32 m0, s44
	v_mfma_f32_16x16x32_bf16 v[48:51], v[214:217], v[166:169], v[48:51]
	global_load_lds_dwordx4 v146, s[48:49]
	s_waitcnt lgkmcnt(1)
	v_mfma_f32_16x16x32_bf16 v[174:177], v[218:221], v[166:169], v[174:177]
	ds_read_b128 v[166:169], v6 offset:9216
	v_mfma_f32_16x16x32_bf16 v[64:67], v[214:217], v[178:181], v[64:67]
	v_mfma_f32_16x16x32_bf16 v[170:173], v[218:221], v[178:181], v[170:173]
	ds_read_b128 v[178:181], v6 offset:11264
	v_mfma_f32_16x16x32_bf16 v[80:83], v[214:217], v[222:225], v[80:83]
	v_mfma_f32_16x16x32_bf16 v[32:35], v[218:221], v[222:225], v[32:35]
	ds_read_b128 v[222:225], v6 offset:13312
	s_waitcnt lgkmcnt(3)
	v_mfma_f32_16x16x32_bf16 v[88:91], v[158:161], v[226:229], v[88:91]
	v_mfma_f32_16x16x32_bf16 v[92:95], v[162:165], v[226:229], v[92:95]
	v_mfma_f32_16x16x32_bf16 v[96:99], v[214:217], v[226:229], v[96:99]
	v_mfma_f32_16x16x32_bf16 v[36:39], v[218:221], v[226:229], v[36:39]
	ds_read_b128 v[226:229], v6 offset:15360
	s_waitcnt lgkmcnt(3)
	v_mfma_f32_16x16x32_bf16 v[104:107], v[158:161], v[166:169], v[104:107]
	v_mfma_f32_16x16x32_bf16 v[108:111], v[162:165], v[166:169], v[108:111]
	v_mfma_f32_16x16x32_bf16 v[112:115], v[214:217], v[166:169], v[112:115]
	v_mfma_f32_16x16x32_bf16 v[52:55], v[218:221], v[166:169], v[52:55]
	s_waitcnt lgkmcnt(2)
	v_mfma_f32_16x16x32_bf16 v[116:119], v[158:161], v[178:181], v[116:119]
	v_mfma_f32_16x16x32_bf16 v[120:123], v[162:165], v[178:181], v[120:123]
	v_mfma_f32_16x16x32_bf16 v[124:127], v[214:217], v[178:181], v[124:127]
	v_mfma_f32_16x16x32_bf16 v[68:71], v[218:221], v[178:181], v[68:71]
	s_waitcnt lgkmcnt(1)
	v_mfma_f32_16x16x32_bf16 v[128:131], v[158:161], v[222:225], v[128:131]
	v_mfma_f32_16x16x32_bf16 v[132:135], v[162:165], v[222:225], v[132:135]
	v_mfma_f32_16x16x32_bf16 v[136:139], v[214:217], v[222:225], v[136:139]
	v_mfma_f32_16x16x32_bf16 v[84:87], v[218:221], v[222:225], v[84:87]
	s_waitcnt lgkmcnt(0)
	v_mfma_f32_16x16x32_bf16 v[100:103], v[158:161], v[226:229], v[100:103]
	v_mfma_f32_16x16x32_bf16 v[140:143], v[162:165], v[226:229], v[140:143]
	v_mfma_f32_16x16x32_bf16 v[150:153], v[214:217], v[226:229], v[150:153]
	v_mfma_f32_16x16x32_bf16 v[154:157], v[218:221], v[226:229], v[154:157]
	s_add_u32 s46, s0, 0x1700
	s_addc_u32 s47, s1, 0
	s_add_u32 s48, s14, 0x1700
	s_waitcnt vmcnt(0)
	s_barrier
	s_addc_u32 s49, s15, 0
	ds_read_b128 v[158:161], v8
	ds_read_b128 v[162:165], v12
	ds_read_b128 v[166:169], v9
	ds_read_b128 v[178:181], v13
	ds_read_b128 v[214:217], v11
	ds_read_b128 v[218:221], v10
	ds_read_b128 v[222:225], v14
	ds_read_b128 v[226:229], v15
	s_waitcnt lgkmcnt(6)
	v_mfma_f32_16x16x32_bf16 v[40:43], v[158:161], v[162:165], v[40:43]
	s_waitcnt lgkmcnt(5)
	v_mfma_f32_16x16x32_bf16 v[44:47], v[166:169], v[162:165], v[44:47]
	s_waitcnt lgkmcnt(4)
	v_mfma_f32_16x16x32_bf16 v[56:59], v[158:161], v[178:181], v[56:59]
	s_mov_b32 m0, s27
	v_mfma_f32_16x16x32_bf16 v[60:63], v[166:169], v[178:181], v[60:63]
	global_load_lds_dwordx4 v0, s[46:47]
	s_waitcnt lgkmcnt(3)
	v_mfma_f32_16x16x32_bf16 v[48:51], v[214:217], v[162:165], v[48:51]
	v_mfma_f32_16x16x32_bf16 v[64:67], v[214:217], v[178:181], v[64:67]
	s_waitcnt lgkmcnt(2)
	v_mfma_f32_16x16x32_bf16 v[174:177], v[218:221], v[162:165], v[174:177]
	ds_read_b128 v[162:165], v16
	v_mfma_f32_16x16x32_bf16 v[170:173], v[218:221], v[178:181], v[170:173]
	ds_read_b128 v[178:181], v17
	s_waitcnt lgkmcnt(3)
	s_mov_b32 m0, s28
	v_mfma_f32_16x16x32_bf16 v[72:75], v[158:161], v[222:225], v[72:75]
	global_load_lds_dwordx4 v0, s[48:49]
	v_mfma_f32_16x16x32_bf16 v[76:79], v[166:169], v[222:225], v[76:79]
	v_mfma_f32_16x16x32_bf16 v[80:83], v[214:217], v[222:225], v[80:83]
	v_mfma_f32_16x16x32_bf16 v[32:35], v[218:221], v[222:225], v[32:35]
	ds_read_b128 v[222:225], v18
	s_waitcnt lgkmcnt(3)
	v_mfma_f32_16x16x32_bf16 v[88:91], v[158:161], v[226:229], v[88:91]
	s_mov_b32 m0, s29
	v_mfma_f32_16x16x32_bf16 v[92:95], v[166:169], v[226:229], v[92:95]
	global_load_lds_dwordx4 v2, s[46:47]
	v_mfma_f32_16x16x32_bf16 v[96:99], v[214:217], v[226:229], v[96:99]
	v_mfma_f32_16x16x32_bf16 v[36:39], v[218:221], v[226:229], v[36:39]
	ds_read_b128 v[226:229], v19
	s_waitcnt lgkmcnt(3)
	v_mfma_f32_16x16x32_bf16 v[104:107], v[158:161], v[162:165], v[104:107]
	s_waitcnt lgkmcnt(2)
	v_mfma_f32_16x16x32_bf16 v[116:119], v[158:161], v[178:181], v[116:119]
	s_waitcnt lgkmcnt(1)
	s_mov_b32 m0, s30
	v_mfma_f32_16x16x32_bf16 v[128:131], v[158:161], v[222:225], v[128:131]
	global_load_lds_dwordx4 v2, s[48:49]
	s_waitcnt lgkmcnt(0)
	v_mfma_f32_16x16x32_bf16 v[100:103], v[158:161], v[226:229], v[100:103]
	ds_read_b128 v[158:161], v20
	v_mfma_f32_16x16x32_bf16 v[108:111], v[166:169], v[162:165], v[108:111]
	v_mfma_f32_16x16x32_bf16 v[120:123], v[166:169], v[178:181], v[120:123]
	v_mfma_f32_16x16x32_bf16 v[132:135], v[166:169], v[222:225], v[132:135]
	s_mov_b32 m0, s31
	v_mfma_f32_16x16x32_bf16 v[140:143], v[166:169], v[226:229], v[140:143]
	global_load_lds_dwordx4 v4, s[46:47]
	ds_read_b128 v[166:169], v24
	v_mfma_f32_16x16x32_bf16 v[112:115], v[214:217], v[162:165], v[112:115]
	v_mfma_f32_16x16x32_bf16 v[52:55], v[218:221], v[162:165], v[52:55]
	ds_read_b128 v[162:165], v21
	v_mfma_f32_16x16x32_bf16 v[124:127], v[214:217], v[178:181], v[124:127]
	v_mfma_f32_16x16x32_bf16 v[68:71], v[218:221], v[178:181], v[68:71]
	ds_read_b128 v[178:181], v25
	s_mov_b32 m0, s34
	v_mfma_f32_16x16x32_bf16 v[136:139], v[214:217], v[222:225], v[136:139]
	global_load_lds_dwordx4 v4, s[48:49]
	v_mfma_f32_16x16x32_bf16 v[84:87], v[218:221], v[222:225], v[84:87]
	ds_read_b128 v[222:225], v26
	v_mfma_f32_16x16x32_bf16 v[150:153], v[214:217], v[226:229], v[150:153]
	ds_read_b128 v[214:217], v23
	v_mfma_f32_16x16x32_bf16 v[154:157], v[218:221], v[226:229], v[154:157]
	ds_read_b128 v[218:221], v22
	ds_read_b128 v[226:229], v27
	s_waitcnt lgkmcnt(6)
	v_mfma_f32_16x16x32_bf16 v[40:43], v[158:161], v[166:169], v[40:43]
	s_waitcnt lgkmcnt(5)
	s_mov_b32 m0, s35
	v_mfma_f32_16x16x32_bf16 v[44:47], v[162:165], v[166:169], v[44:47]
	global_load_lds_dwordx4 v146, s[46:47]
	s_waitcnt lgkmcnt(4)
	v_mfma_f32_16x16x32_bf16 v[56:59], v[158:161], v[178:181], v[56:59]
	v_mfma_f32_16x16x32_bf16 v[60:63], v[162:165], v[178:181], v[60:63]
	s_waitcnt lgkmcnt(3)
	v_mfma_f32_16x16x32_bf16 v[72:75], v[158:161], v[222:225], v[72:75]
	v_mfma_f32_16x16x32_bf16 v[76:79], v[162:165], v[222:225], v[76:79]
	s_waitcnt lgkmcnt(2)
	s_mov_b32 m0, s36
	v_mfma_f32_16x16x32_bf16 v[48:51], v[214:217], v[166:169], v[48:51]
	global_load_lds_dwordx4 v146, s[48:49]
	s_waitcnt lgkmcnt(1)
	v_mfma_f32_16x16x32_bf16 v[174:177], v[218:221], v[166:169], v[174:177]
	ds_read_b128 v[166:169], v28
	v_mfma_f32_16x16x32_bf16 v[64:67], v[214:217], v[178:181], v[64:67]
	v_mfma_f32_16x16x32_bf16 v[170:173], v[218:221], v[178:181], v[170:173]
	ds_read_b128 v[178:181], v29
	v_mfma_f32_16x16x32_bf16 v[80:83], v[214:217], v[222:225], v[80:83]
	v_mfma_f32_16x16x32_bf16 v[32:35], v[218:221], v[222:225], v[32:35]
	ds_read_b128 v[222:225], v30
	s_waitcnt lgkmcnt(3)
	v_mfma_f32_16x16x32_bf16 v[88:91], v[158:161], v[226:229], v[88:91]
	v_mfma_f32_16x16x32_bf16 v[92:95], v[162:165], v[226:229], v[92:95]
	v_mfma_f32_16x16x32_bf16 v[96:99], v[214:217], v[226:229], v[96:99]
	v_mfma_f32_16x16x32_bf16 v[36:39], v[218:221], v[226:229], v[36:39]
	ds_read_b128 v[226:229], v31
	s_waitcnt lgkmcnt(3)
	v_mfma_f32_16x16x32_bf16 v[104:107], v[158:161], v[166:169], v[104:107]
	v_mfma_f32_16x16x32_bf16 v[108:111], v[162:165], v[166:169], v[108:111]
	v_mfma_f32_16x16x32_bf16 v[112:115], v[214:217], v[166:169], v[112:115]
	v_mfma_f32_16x16x32_bf16 v[52:55], v[218:221], v[166:169], v[52:55]
	s_waitcnt lgkmcnt(2)
	v_mfma_f32_16x16x32_bf16 v[116:119], v[158:161], v[178:181], v[116:119]
	v_mfma_f32_16x16x32_bf16 v[120:123], v[162:165], v[178:181], v[120:123]
	v_mfma_f32_16x16x32_bf16 v[124:127], v[214:217], v[178:181], v[124:127]
	v_mfma_f32_16x16x32_bf16 v[68:71], v[218:221], v[178:181], v[68:71]
	s_waitcnt lgkmcnt(1)
	v_mfma_f32_16x16x32_bf16 v[128:131], v[158:161], v[222:225], v[128:131]
	v_mfma_f32_16x16x32_bf16 v[132:135], v[162:165], v[222:225], v[132:135]
	v_mfma_f32_16x16x32_bf16 v[136:139], v[214:217], v[222:225], v[136:139]
	v_mfma_f32_16x16x32_bf16 v[84:87], v[218:221], v[222:225], v[84:87]
	s_waitcnt lgkmcnt(0)
	v_mfma_f32_16x16x32_bf16 v[100:103], v[158:161], v[226:229], v[100:103]
	v_mfma_f32_16x16x32_bf16 v[140:143], v[162:165], v[226:229], v[140:143]
	v_mfma_f32_16x16x32_bf16 v[150:153], v[214:217], v[226:229], v[150:153]
	v_mfma_f32_16x16x32_bf16 v[154:157], v[218:221], v[226:229], v[154:157]
	s_add_u32 s46, s0, 0x1780
	s_addc_u32 s47, s1, 0
	s_add_u32 s48, s14, 0x1780
	s_waitcnt vmcnt(0)
	s_barrier
	s_addc_u32 s49, s15, 0
	ds_read_b128 v[158:161], v7 offset:32768
	ds_read_b128 v[162:165], v6
	ds_read_b128 v[166:169], v7 offset:34816
	ds_read_b128 v[178:181], v6 offset:2048
	ds_read_b128 v[214:217], v7 offset:36864
	ds_read_b128 v[218:221], v7 offset:38912
	ds_read_b128 v[222:225], v6 offset:4096
	ds_read_b128 v[226:229], v6 offset:6144
	s_waitcnt lgkmcnt(6)
	v_mfma_f32_16x16x32_bf16 v[40:43], v[158:161], v[162:165], v[40:43]
	s_waitcnt lgkmcnt(5)
	v_mfma_f32_16x16x32_bf16 v[44:47], v[166:169], v[162:165], v[44:47]
	s_waitcnt lgkmcnt(4)
	v_mfma_f32_16x16x32_bf16 v[56:59], v[158:161], v[178:181], v[56:59]
	s_mov_b32 m0, s38
	v_mfma_f32_16x16x32_bf16 v[60:63], v[166:169], v[178:181], v[60:63]
	global_load_lds_dwordx4 v0, s[46:47]
	s_waitcnt lgkmcnt(3)
	v_mfma_f32_16x16x32_bf16 v[48:51], v[214:217], v[162:165], v[48:51]
	v_mfma_f32_16x16x32_bf16 v[64:67], v[214:217], v[178:181], v[64:67]
	s_waitcnt lgkmcnt(2)
	v_mfma_f32_16x16x32_bf16 v[174:177], v[218:221], v[162:165], v[174:177]
	ds_read_b128 v[162:165], v6 offset:8192
	v_mfma_f32_16x16x32_bf16 v[170:173], v[218:221], v[178:181], v[170:173]
	ds_read_b128 v[178:181], v6 offset:10240
	s_waitcnt lgkmcnt(3)
	s_mov_b32 m0, s37
	v_mfma_f32_16x16x32_bf16 v[72:75], v[158:161], v[222:225], v[72:75]
	global_load_lds_dwordx4 v0, s[48:49]
	v_mfma_f32_16x16x32_bf16 v[76:79], v[166:169], v[222:225], v[76:79]
	v_mfma_f32_16x16x32_bf16 v[80:83], v[214:217], v[222:225], v[80:83]
	v_mfma_f32_16x16x32_bf16 v[32:35], v[218:221], v[222:225], v[32:35]
	ds_read_b128 v[222:225], v6 offset:12288
	s_waitcnt lgkmcnt(3)
	v_mfma_f32_16x16x32_bf16 v[88:91], v[158:161], v[226:229], v[88:91]
	s_mov_b32 m0, s39
	v_mfma_f32_16x16x32_bf16 v[92:95], v[166:169], v[226:229], v[92:95]
	global_load_lds_dwordx4 v2, s[46:47]
	v_mfma_f32_16x16x32_bf16 v[96:99], v[214:217], v[226:229], v[96:99]
	v_mfma_f32_16x16x32_bf16 v[36:39], v[218:221], v[226:229], v[36:39]
	ds_read_b128 v[226:229], v6 offset:14336
	s_waitcnt lgkmcnt(3)
	v_mfma_f32_16x16x32_bf16 v[104:107], v[158:161], v[162:165], v[104:107]
	s_waitcnt lgkmcnt(2)
	v_mfma_f32_16x16x32_bf16 v[116:119], v[158:161], v[178:181], v[116:119]
	s_waitcnt lgkmcnt(1)
	s_mov_b32 m0, s40
	v_mfma_f32_16x16x32_bf16 v[128:131], v[158:161], v[222:225], v[128:131]
	global_load_lds_dwordx4 v2, s[48:49]
	s_waitcnt lgkmcnt(0)
	v_mfma_f32_16x16x32_bf16 v[100:103], v[158:161], v[226:229], v[100:103]
	ds_read_b128 v[158:161], v7 offset:33792
	v_mfma_f32_16x16x32_bf16 v[108:111], v[166:169], v[162:165], v[108:111]
	v_mfma_f32_16x16x32_bf16 v[120:123], v[166:169], v[178:181], v[120:123]
	v_mfma_f32_16x16x32_bf16 v[132:135], v[166:169], v[222:225], v[132:135]
	s_mov_b32 m0, s41
	v_mfma_f32_16x16x32_bf16 v[140:143], v[166:169], v[226:229], v[140:143]
	global_load_lds_dwordx4 v4, s[46:47]
	ds_read_b128 v[166:169], v6 offset:1024
	v_mfma_f32_16x16x32_bf16 v[112:115], v[214:217], v[162:165], v[112:115]
	v_mfma_f32_16x16x32_bf16 v[52:55], v[218:221], v[162:165], v[52:55]
	ds_read_b128 v[162:165], v7 offset:35840
	v_mfma_f32_16x16x32_bf16 v[124:127], v[214:217], v[178:181], v[124:127]
	v_mfma_f32_16x16x32_bf16 v[68:71], v[218:221], v[178:181], v[68:71]
	ds_read_b128 v[178:181], v6 offset:3072
	s_mov_b32 m0, s42
	v_mfma_f32_16x16x32_bf16 v[136:139], v[214:217], v[222:225], v[136:139]
	global_load_lds_dwordx4 v4, s[48:49]
	v_mfma_f32_16x16x32_bf16 v[84:87], v[218:221], v[222:225], v[84:87]
	ds_read_b128 v[222:225], v6 offset:5120
	v_mfma_f32_16x16x32_bf16 v[150:153], v[214:217], v[226:229], v[150:153]
	ds_read_b128 v[214:217], v7 offset:37888
	v_mfma_f32_16x16x32_bf16 v[154:157], v[218:221], v[226:229], v[154:157]
	ds_read_b128 v[218:221], v7 offset:39936
	ds_read_b128 v[226:229], v6 offset:7168
	s_waitcnt lgkmcnt(6)
	v_mfma_f32_16x16x32_bf16 v[40:43], v[158:161], v[166:169], v[40:43]
	s_waitcnt lgkmcnt(5)
	s_mov_b32 m0, s43
	v_mfma_f32_16x16x32_bf16 v[44:47], v[162:165], v[166:169], v[44:47]
	global_load_lds_dwordx4 v146, s[46:47]
	s_waitcnt lgkmcnt(4)
	v_mfma_f32_16x16x32_bf16 v[56:59], v[158:161], v[178:181], v[56:59]
	v_mfma_f32_16x16x32_bf16 v[60:63], v[162:165], v[178:181], v[60:63]
	s_waitcnt lgkmcnt(3)
	v_mfma_f32_16x16x32_bf16 v[72:75], v[158:161], v[222:225], v[72:75]
	v_mfma_f32_16x16x32_bf16 v[76:79], v[162:165], v[222:225], v[76:79]
	s_waitcnt lgkmcnt(2)
	s_mov_b32 m0, s44
	v_mfma_f32_16x16x32_bf16 v[48:51], v[214:217], v[166:169], v[48:51]
	global_load_lds_dwordx4 v146, s[48:49]
	s_waitcnt lgkmcnt(1)
	v_mfma_f32_16x16x32_bf16 v[174:177], v[218:221], v[166:169], v[174:177]
	ds_read_b128 v[166:169], v6 offset:9216
	v_mfma_f32_16x16x32_bf16 v[64:67], v[214:217], v[178:181], v[64:67]
	v_mfma_f32_16x16x32_bf16 v[170:173], v[218:221], v[178:181], v[170:173]
	ds_read_b128 v[178:181], v6 offset:11264
	v_mfma_f32_16x16x32_bf16 v[80:83], v[214:217], v[222:225], v[80:83]
	v_mfma_f32_16x16x32_bf16 v[32:35], v[218:221], v[222:225], v[32:35]
	ds_read_b128 v[222:225], v6 offset:13312
	s_waitcnt lgkmcnt(3)
	v_mfma_f32_16x16x32_bf16 v[88:91], v[158:161], v[226:229], v[88:91]
	v_mfma_f32_16x16x32_bf16 v[92:95], v[162:165], v[226:229], v[92:95]
	v_mfma_f32_16x16x32_bf16 v[96:99], v[214:217], v[226:229], v[96:99]
	v_mfma_f32_16x16x32_bf16 v[36:39], v[218:221], v[226:229], v[36:39]
	ds_read_b128 v[226:229], v6 offset:15360
	s_waitcnt lgkmcnt(3)
	v_mfma_f32_16x16x32_bf16 v[104:107], v[158:161], v[166:169], v[104:107]
	v_mfma_f32_16x16x32_bf16 v[108:111], v[162:165], v[166:169], v[108:111]
	v_mfma_f32_16x16x32_bf16 v[112:115], v[214:217], v[166:169], v[112:115]
	v_mfma_f32_16x16x32_bf16 v[52:55], v[218:221], v[166:169], v[52:55]
	s_waitcnt lgkmcnt(2)
	v_mfma_f32_16x16x32_bf16 v[116:119], v[158:161], v[178:181], v[116:119]
	v_mfma_f32_16x16x32_bf16 v[120:123], v[162:165], v[178:181], v[120:123]
	v_mfma_f32_16x16x32_bf16 v[124:127], v[214:217], v[178:181], v[124:127]
	v_mfma_f32_16x16x32_bf16 v[68:71], v[218:221], v[178:181], v[68:71]
	s_waitcnt lgkmcnt(1)
	v_mfma_f32_16x16x32_bf16 v[128:131], v[158:161], v[222:225], v[128:131]
	v_mfma_f32_16x16x32_bf16 v[132:135], v[162:165], v[222:225], v[132:135]
	v_mfma_f32_16x16x32_bf16 v[136:139], v[214:217], v[222:225], v[136:139]
	v_mfma_f32_16x16x32_bf16 v[84:87], v[218:221], v[222:225], v[84:87]
	s_waitcnt lgkmcnt(0)
	v_mfma_f32_16x16x32_bf16 v[100:103], v[158:161], v[226:229], v[100:103]
	v_mfma_f32_16x16x32_bf16 v[140:143], v[162:165], v[226:229], v[140:143]
	v_mfma_f32_16x16x32_bf16 v[150:153], v[214:217], v[226:229], v[150:153]
	v_mfma_f32_16x16x32_bf16 v[154:157], v[218:221], v[226:229], v[154:157]
	s_add_u32 s46, s0, 0x1800
	s_addc_u32 s47, s1, 0
	s_add_u32 s48, s14, 0x1800
	s_waitcnt vmcnt(0)
	s_barrier
	s_addc_u32 s49, s15, 0
	ds_read_b128 v[158:161], v8
	ds_read_b128 v[162:165], v12
	ds_read_b128 v[166:169], v9
	ds_read_b128 v[178:181], v13
	ds_read_b128 v[214:217], v11
	ds_read_b128 v[218:221], v10
	ds_read_b128 v[222:225], v14
	ds_read_b128 v[226:229], v15
	s_waitcnt lgkmcnt(6)
	v_mfma_f32_16x16x32_bf16 v[40:43], v[158:161], v[162:165], v[40:43]
	s_waitcnt lgkmcnt(5)
	v_mfma_f32_16x16x32_bf16 v[44:47], v[166:169], v[162:165], v[44:47]
	s_waitcnt lgkmcnt(4)
	v_mfma_f32_16x16x32_bf16 v[56:59], v[158:161], v[178:181], v[56:59]
	s_mov_b32 m0, s27
	v_mfma_f32_16x16x32_bf16 v[60:63], v[166:169], v[178:181], v[60:63]
	global_load_lds_dwordx4 v0, s[46:47]
	s_waitcnt lgkmcnt(3)
	v_mfma_f32_16x16x32_bf16 v[48:51], v[214:217], v[162:165], v[48:51]
	v_mfma_f32_16x16x32_bf16 v[64:67], v[214:217], v[178:181], v[64:67]
	s_waitcnt lgkmcnt(2)
	v_mfma_f32_16x16x32_bf16 v[174:177], v[218:221], v[162:165], v[174:177]
	ds_read_b128 v[162:165], v16
	v_mfma_f32_16x16x32_bf16 v[170:173], v[218:221], v[178:181], v[170:173]
	ds_read_b128 v[178:181], v17
	s_waitcnt lgkmcnt(3)
	s_mov_b32 m0, s28
	v_mfma_f32_16x16x32_bf16 v[72:75], v[158:161], v[222:225], v[72:75]
	global_load_lds_dwordx4 v0, s[48:49]
	v_mfma_f32_16x16x32_bf16 v[76:79], v[166:169], v[222:225], v[76:79]
	v_mfma_f32_16x16x32_bf16 v[80:83], v[214:217], v[222:225], v[80:83]
	v_mfma_f32_16x16x32_bf16 v[32:35], v[218:221], v[222:225], v[32:35]
	ds_read_b128 v[222:225], v18
	s_waitcnt lgkmcnt(3)
	v_mfma_f32_16x16x32_bf16 v[88:91], v[158:161], v[226:229], v[88:91]
	s_mov_b32 m0, s29
	v_mfma_f32_16x16x32_bf16 v[92:95], v[166:169], v[226:229], v[92:95]
	global_load_lds_dwordx4 v2, s[46:47]
	v_mfma_f32_16x16x32_bf16 v[96:99], v[214:217], v[226:229], v[96:99]
	v_mfma_f32_16x16x32_bf16 v[36:39], v[218:221], v[226:229], v[36:39]
	ds_read_b128 v[226:229], v19
	s_waitcnt lgkmcnt(3)
	v_mfma_f32_16x16x32_bf16 v[104:107], v[158:161], v[162:165], v[104:107]
	s_waitcnt lgkmcnt(2)
	v_mfma_f32_16x16x32_bf16 v[116:119], v[158:161], v[178:181], v[116:119]
	s_waitcnt lgkmcnt(1)
	s_mov_b32 m0, s30
	v_mfma_f32_16x16x32_bf16 v[128:131], v[158:161], v[222:225], v[128:131]
	global_load_lds_dwordx4 v2, s[48:49]
	s_waitcnt lgkmcnt(0)
	v_mfma_f32_16x16x32_bf16 v[100:103], v[158:161], v[226:229], v[100:103]
	ds_read_b128 v[158:161], v20
	v_mfma_f32_16x16x32_bf16 v[108:111], v[166:169], v[162:165], v[108:111]
	v_mfma_f32_16x16x32_bf16 v[120:123], v[166:169], v[178:181], v[120:123]
	v_mfma_f32_16x16x32_bf16 v[132:135], v[166:169], v[222:225], v[132:135]
	s_mov_b32 m0, s31
	v_mfma_f32_16x16x32_bf16 v[140:143], v[166:169], v[226:229], v[140:143]
	global_load_lds_dwordx4 v4, s[46:47]
	ds_read_b128 v[166:169], v24
	v_mfma_f32_16x16x32_bf16 v[112:115], v[214:217], v[162:165], v[112:115]
	v_mfma_f32_16x16x32_bf16 v[52:55], v[218:221], v[162:165], v[52:55]
	ds_read_b128 v[162:165], v21
	v_mfma_f32_16x16x32_bf16 v[124:127], v[214:217], v[178:181], v[124:127]
	v_mfma_f32_16x16x32_bf16 v[68:71], v[218:221], v[178:181], v[68:71]
	ds_read_b128 v[178:181], v25
	s_mov_b32 m0, s34
	v_mfma_f32_16x16x32_bf16 v[136:139], v[214:217], v[222:225], v[136:139]
	global_load_lds_dwordx4 v4, s[48:49]
	v_mfma_f32_16x16x32_bf16 v[84:87], v[218:221], v[222:225], v[84:87]
	ds_read_b128 v[222:225], v26
	v_mfma_f32_16x16x32_bf16 v[150:153], v[214:217], v[226:229], v[150:153]
	ds_read_b128 v[214:217], v23
	v_mfma_f32_16x16x32_bf16 v[154:157], v[218:221], v[226:229], v[154:157]
	ds_read_b128 v[218:221], v22
	ds_read_b128 v[226:229], v27
	s_waitcnt lgkmcnt(6)
	v_mfma_f32_16x16x32_bf16 v[40:43], v[158:161], v[166:169], v[40:43]
	s_waitcnt lgkmcnt(5)
	s_mov_b32 m0, s35
	v_mfma_f32_16x16x32_bf16 v[44:47], v[162:165], v[166:169], v[44:47]
	global_load_lds_dwordx4 v146, s[46:47]
	s_waitcnt lgkmcnt(4)
	v_mfma_f32_16x16x32_bf16 v[56:59], v[158:161], v[178:181], v[56:59]
	v_mfma_f32_16x16x32_bf16 v[60:63], v[162:165], v[178:181], v[60:63]
	s_waitcnt lgkmcnt(3)
	v_mfma_f32_16x16x32_bf16 v[72:75], v[158:161], v[222:225], v[72:75]
	v_mfma_f32_16x16x32_bf16 v[76:79], v[162:165], v[222:225], v[76:79]
	s_waitcnt lgkmcnt(2)
	s_mov_b32 m0, s36
	v_mfma_f32_16x16x32_bf16 v[48:51], v[214:217], v[166:169], v[48:51]
	global_load_lds_dwordx4 v146, s[48:49]
	s_waitcnt lgkmcnt(1)
	v_mfma_f32_16x16x32_bf16 v[174:177], v[218:221], v[166:169], v[174:177]
	ds_read_b128 v[166:169], v28
	v_mfma_f32_16x16x32_bf16 v[64:67], v[214:217], v[178:181], v[64:67]
	v_mfma_f32_16x16x32_bf16 v[170:173], v[218:221], v[178:181], v[170:173]
	ds_read_b128 v[178:181], v29
	v_mfma_f32_16x16x32_bf16 v[80:83], v[214:217], v[222:225], v[80:83]
	v_mfma_f32_16x16x32_bf16 v[32:35], v[218:221], v[222:225], v[32:35]
	ds_read_b128 v[222:225], v30
	s_waitcnt lgkmcnt(3)
	v_mfma_f32_16x16x32_bf16 v[88:91], v[158:161], v[226:229], v[88:91]
	v_mfma_f32_16x16x32_bf16 v[92:95], v[162:165], v[226:229], v[92:95]
	v_mfma_f32_16x16x32_bf16 v[96:99], v[214:217], v[226:229], v[96:99]
	v_mfma_f32_16x16x32_bf16 v[36:39], v[218:221], v[226:229], v[36:39]
	ds_read_b128 v[226:229], v31
	s_waitcnt lgkmcnt(3)
	v_mfma_f32_16x16x32_bf16 v[104:107], v[158:161], v[166:169], v[104:107]
	v_mfma_f32_16x16x32_bf16 v[108:111], v[162:165], v[166:169], v[108:111]
	v_mfma_f32_16x16x32_bf16 v[112:115], v[214:217], v[166:169], v[112:115]
	v_mfma_f32_16x16x32_bf16 v[52:55], v[218:221], v[166:169], v[52:55]
	s_waitcnt lgkmcnt(2)
	v_mfma_f32_16x16x32_bf16 v[116:119], v[158:161], v[178:181], v[116:119]
	v_mfma_f32_16x16x32_bf16 v[120:123], v[162:165], v[178:181], v[120:123]
	v_mfma_f32_16x16x32_bf16 v[124:127], v[214:217], v[178:181], v[124:127]
	v_mfma_f32_16x16x32_bf16 v[68:71], v[218:221], v[178:181], v[68:71]
	s_waitcnt lgkmcnt(1)
	v_mfma_f32_16x16x32_bf16 v[128:131], v[158:161], v[222:225], v[128:131]
	v_mfma_f32_16x16x32_bf16 v[132:135], v[162:165], v[222:225], v[132:135]
	v_mfma_f32_16x16x32_bf16 v[136:139], v[214:217], v[222:225], v[136:139]
	v_mfma_f32_16x16x32_bf16 v[84:87], v[218:221], v[222:225], v[84:87]
	s_waitcnt lgkmcnt(0)
	v_mfma_f32_16x16x32_bf16 v[100:103], v[158:161], v[226:229], v[100:103]
	v_mfma_f32_16x16x32_bf16 v[140:143], v[162:165], v[226:229], v[140:143]
	v_mfma_f32_16x16x32_bf16 v[150:153], v[214:217], v[226:229], v[150:153]
	v_mfma_f32_16x16x32_bf16 v[154:157], v[218:221], v[226:229], v[154:157]
	s_add_u32 s46, s0, 0x1880
	s_addc_u32 s47, s1, 0
	s_add_u32 s48, s14, 0x1880
	s_waitcnt vmcnt(0)
	s_barrier
	s_addc_u32 s49, s15, 0
	ds_read_b128 v[158:161], v7 offset:32768
	ds_read_b128 v[162:165], v6
	ds_read_b128 v[166:169], v7 offset:34816
	ds_read_b128 v[178:181], v6 offset:2048
	ds_read_b128 v[214:217], v7 offset:36864
	ds_read_b128 v[218:221], v7 offset:38912
	ds_read_b128 v[222:225], v6 offset:4096
	ds_read_b128 v[226:229], v6 offset:6144
	s_waitcnt lgkmcnt(6)
	v_mfma_f32_16x16x32_bf16 v[40:43], v[158:161], v[162:165], v[40:43]
	s_waitcnt lgkmcnt(5)
	v_mfma_f32_16x16x32_bf16 v[44:47], v[166:169], v[162:165], v[44:47]
	s_waitcnt lgkmcnt(4)
	v_mfma_f32_16x16x32_bf16 v[56:59], v[158:161], v[178:181], v[56:59]
	s_mov_b32 m0, s38
	v_mfma_f32_16x16x32_bf16 v[60:63], v[166:169], v[178:181], v[60:63]
	global_load_lds_dwordx4 v0, s[46:47]
	s_waitcnt lgkmcnt(3)
	v_mfma_f32_16x16x32_bf16 v[48:51], v[214:217], v[162:165], v[48:51]
	v_mfma_f32_16x16x32_bf16 v[64:67], v[214:217], v[178:181], v[64:67]
	s_waitcnt lgkmcnt(2)
	v_mfma_f32_16x16x32_bf16 v[174:177], v[218:221], v[162:165], v[174:177]
	ds_read_b128 v[162:165], v6 offset:8192
	v_mfma_f32_16x16x32_bf16 v[170:173], v[218:221], v[178:181], v[170:173]
	ds_read_b128 v[178:181], v6 offset:10240
	s_waitcnt lgkmcnt(3)
	s_mov_b32 m0, s37
	v_mfma_f32_16x16x32_bf16 v[72:75], v[158:161], v[222:225], v[72:75]
	global_load_lds_dwordx4 v0, s[48:49]
	v_mfma_f32_16x16x32_bf16 v[76:79], v[166:169], v[222:225], v[76:79]
	v_mfma_f32_16x16x32_bf16 v[80:83], v[214:217], v[222:225], v[80:83]
	v_mfma_f32_16x16x32_bf16 v[32:35], v[218:221], v[222:225], v[32:35]
	ds_read_b128 v[222:225], v6 offset:12288
	s_waitcnt lgkmcnt(3)
	v_mfma_f32_16x16x32_bf16 v[88:91], v[158:161], v[226:229], v[88:91]
	s_mov_b32 m0, s39
	v_mfma_f32_16x16x32_bf16 v[92:95], v[166:169], v[226:229], v[92:95]
	global_load_lds_dwordx4 v2, s[46:47]
	v_mfma_f32_16x16x32_bf16 v[96:99], v[214:217], v[226:229], v[96:99]
	v_mfma_f32_16x16x32_bf16 v[36:39], v[218:221], v[226:229], v[36:39]
	ds_read_b128 v[226:229], v6 offset:14336
	s_waitcnt lgkmcnt(3)
	v_mfma_f32_16x16x32_bf16 v[104:107], v[158:161], v[162:165], v[104:107]
	s_waitcnt lgkmcnt(2)
	v_mfma_f32_16x16x32_bf16 v[116:119], v[158:161], v[178:181], v[116:119]
	s_waitcnt lgkmcnt(1)
	s_mov_b32 m0, s40
	v_mfma_f32_16x16x32_bf16 v[128:131], v[158:161], v[222:225], v[128:131]
	global_load_lds_dwordx4 v2, s[48:49]
	s_waitcnt lgkmcnt(0)
	v_mfma_f32_16x16x32_bf16 v[100:103], v[158:161], v[226:229], v[100:103]
	ds_read_b128 v[158:161], v7 offset:33792
	v_mfma_f32_16x16x32_bf16 v[108:111], v[166:169], v[162:165], v[108:111]
	v_mfma_f32_16x16x32_bf16 v[120:123], v[166:169], v[178:181], v[120:123]
	v_mfma_f32_16x16x32_bf16 v[132:135], v[166:169], v[222:225], v[132:135]
	s_mov_b32 m0, s41
	v_mfma_f32_16x16x32_bf16 v[140:143], v[166:169], v[226:229], v[140:143]
	global_load_lds_dwordx4 v4, s[46:47]
	ds_read_b128 v[166:169], v6 offset:1024
	v_mfma_f32_16x16x32_bf16 v[112:115], v[214:217], v[162:165], v[112:115]
	v_mfma_f32_16x16x32_bf16 v[52:55], v[218:221], v[162:165], v[52:55]
	ds_read_b128 v[162:165], v7 offset:35840
	v_mfma_f32_16x16x32_bf16 v[124:127], v[214:217], v[178:181], v[124:127]
	v_mfma_f32_16x16x32_bf16 v[68:71], v[218:221], v[178:181], v[68:71]
	ds_read_b128 v[178:181], v6 offset:3072
	s_mov_b32 m0, s42
	v_mfma_f32_16x16x32_bf16 v[136:139], v[214:217], v[222:225], v[136:139]
	global_load_lds_dwordx4 v4, s[48:49]
	v_mfma_f32_16x16x32_bf16 v[84:87], v[218:221], v[222:225], v[84:87]
	ds_read_b128 v[222:225], v6 offset:5120
	v_mfma_f32_16x16x32_bf16 v[150:153], v[214:217], v[226:229], v[150:153]
	ds_read_b128 v[214:217], v7 offset:37888
	v_mfma_f32_16x16x32_bf16 v[154:157], v[218:221], v[226:229], v[154:157]
	ds_read_b128 v[218:221], v7 offset:39936
	ds_read_b128 v[226:229], v6 offset:7168
	s_waitcnt lgkmcnt(6)
	v_mfma_f32_16x16x32_bf16 v[40:43], v[158:161], v[166:169], v[40:43]
	s_waitcnt lgkmcnt(5)
	s_mov_b32 m0, s43
	v_mfma_f32_16x16x32_bf16 v[44:47], v[162:165], v[166:169], v[44:47]
	global_load_lds_dwordx4 v146, s[46:47]
	s_waitcnt lgkmcnt(4)
	v_mfma_f32_16x16x32_bf16 v[56:59], v[158:161], v[178:181], v[56:59]
	v_mfma_f32_16x16x32_bf16 v[60:63], v[162:165], v[178:181], v[60:63]
	s_waitcnt lgkmcnt(3)
	v_mfma_f32_16x16x32_bf16 v[72:75], v[158:161], v[222:225], v[72:75]
	v_mfma_f32_16x16x32_bf16 v[76:79], v[162:165], v[222:225], v[76:79]
	s_waitcnt lgkmcnt(2)
	s_mov_b32 m0, s44
	v_mfma_f32_16x16x32_bf16 v[48:51], v[214:217], v[166:169], v[48:51]
	global_load_lds_dwordx4 v146, s[48:49]
	s_waitcnt lgkmcnt(1)
	v_mfma_f32_16x16x32_bf16 v[174:177], v[218:221], v[166:169], v[174:177]
	ds_read_b128 v[166:169], v6 offset:9216
	v_mfma_f32_16x16x32_bf16 v[64:67], v[214:217], v[178:181], v[64:67]
	v_mfma_f32_16x16x32_bf16 v[170:173], v[218:221], v[178:181], v[170:173]
	ds_read_b128 v[178:181], v6 offset:11264
	v_mfma_f32_16x16x32_bf16 v[80:83], v[214:217], v[222:225], v[80:83]
	v_mfma_f32_16x16x32_bf16 v[32:35], v[218:221], v[222:225], v[32:35]
	ds_read_b128 v[222:225], v6 offset:13312
	s_waitcnt lgkmcnt(3)
	v_mfma_f32_16x16x32_bf16 v[88:91], v[158:161], v[226:229], v[88:91]
	v_mfma_f32_16x16x32_bf16 v[92:95], v[162:165], v[226:229], v[92:95]
	v_mfma_f32_16x16x32_bf16 v[96:99], v[214:217], v[226:229], v[96:99]
	v_mfma_f32_16x16x32_bf16 v[36:39], v[218:221], v[226:229], v[36:39]
	ds_read_b128 v[226:229], v6 offset:15360
	s_waitcnt lgkmcnt(3)
	v_mfma_f32_16x16x32_bf16 v[104:107], v[158:161], v[166:169], v[104:107]
	v_mfma_f32_16x16x32_bf16 v[108:111], v[162:165], v[166:169], v[108:111]
	v_mfma_f32_16x16x32_bf16 v[112:115], v[214:217], v[166:169], v[112:115]
	v_mfma_f32_16x16x32_bf16 v[52:55], v[218:221], v[166:169], v[52:55]
	s_waitcnt lgkmcnt(2)
	v_mfma_f32_16x16x32_bf16 v[116:119], v[158:161], v[178:181], v[116:119]
	v_mfma_f32_16x16x32_bf16 v[120:123], v[162:165], v[178:181], v[120:123]
	v_mfma_f32_16x16x32_bf16 v[124:127], v[214:217], v[178:181], v[124:127]
	v_mfma_f32_16x16x32_bf16 v[68:71], v[218:221], v[178:181], v[68:71]
	s_waitcnt lgkmcnt(1)
	v_mfma_f32_16x16x32_bf16 v[128:131], v[158:161], v[222:225], v[128:131]
	v_mfma_f32_16x16x32_bf16 v[132:135], v[162:165], v[222:225], v[132:135]
	v_mfma_f32_16x16x32_bf16 v[136:139], v[214:217], v[222:225], v[136:139]
	v_mfma_f32_16x16x32_bf16 v[84:87], v[218:221], v[222:225], v[84:87]
	s_waitcnt lgkmcnt(0)
	v_mfma_f32_16x16x32_bf16 v[100:103], v[158:161], v[226:229], v[100:103]
	v_mfma_f32_16x16x32_bf16 v[140:143], v[162:165], v[226:229], v[140:143]
	v_mfma_f32_16x16x32_bf16 v[150:153], v[214:217], v[226:229], v[150:153]
	v_mfma_f32_16x16x32_bf16 v[154:157], v[218:221], v[226:229], v[154:157]
	s_add_u32 s46, s0, 0x1900
	s_addc_u32 s47, s1, 0
	s_add_u32 s48, s14, 0x1900
	s_waitcnt vmcnt(0)
	s_barrier
	s_addc_u32 s49, s15, 0
	ds_read_b128 v[158:161], v8
	ds_read_b128 v[162:165], v12
	ds_read_b128 v[166:169], v9
	ds_read_b128 v[178:181], v13
	ds_read_b128 v[214:217], v11
	ds_read_b128 v[218:221], v10
	ds_read_b128 v[222:225], v14
	ds_read_b128 v[226:229], v15
	s_waitcnt lgkmcnt(6)
	v_mfma_f32_16x16x32_bf16 v[40:43], v[158:161], v[162:165], v[40:43]
	s_waitcnt lgkmcnt(5)
	v_mfma_f32_16x16x32_bf16 v[44:47], v[166:169], v[162:165], v[44:47]
	s_waitcnt lgkmcnt(4)
	v_mfma_f32_16x16x32_bf16 v[56:59], v[158:161], v[178:181], v[56:59]
	s_mov_b32 m0, s27
	v_mfma_f32_16x16x32_bf16 v[60:63], v[166:169], v[178:181], v[60:63]
	global_load_lds_dwordx4 v0, s[46:47]
	s_waitcnt lgkmcnt(3)
	v_mfma_f32_16x16x32_bf16 v[48:51], v[214:217], v[162:165], v[48:51]
	v_mfma_f32_16x16x32_bf16 v[64:67], v[214:217], v[178:181], v[64:67]
	s_waitcnt lgkmcnt(2)
	v_mfma_f32_16x16x32_bf16 v[174:177], v[218:221], v[162:165], v[174:177]
	ds_read_b128 v[162:165], v16
	v_mfma_f32_16x16x32_bf16 v[170:173], v[218:221], v[178:181], v[170:173]
	ds_read_b128 v[178:181], v17
	s_waitcnt lgkmcnt(3)
	s_mov_b32 m0, s28
	v_mfma_f32_16x16x32_bf16 v[72:75], v[158:161], v[222:225], v[72:75]
	global_load_lds_dwordx4 v0, s[48:49]
	v_mfma_f32_16x16x32_bf16 v[76:79], v[166:169], v[222:225], v[76:79]
	v_mfma_f32_16x16x32_bf16 v[80:83], v[214:217], v[222:225], v[80:83]
	v_mfma_f32_16x16x32_bf16 v[32:35], v[218:221], v[222:225], v[32:35]
	ds_read_b128 v[222:225], v18
	s_waitcnt lgkmcnt(3)
	v_mfma_f32_16x16x32_bf16 v[88:91], v[158:161], v[226:229], v[88:91]
	s_mov_b32 m0, s29
	v_mfma_f32_16x16x32_bf16 v[92:95], v[166:169], v[226:229], v[92:95]
	global_load_lds_dwordx4 v2, s[46:47]
	v_mfma_f32_16x16x32_bf16 v[96:99], v[214:217], v[226:229], v[96:99]
	v_mfma_f32_16x16x32_bf16 v[36:39], v[218:221], v[226:229], v[36:39]
	ds_read_b128 v[226:229], v19
	s_waitcnt lgkmcnt(3)
	v_mfma_f32_16x16x32_bf16 v[104:107], v[158:161], v[162:165], v[104:107]
	s_waitcnt lgkmcnt(2)
	v_mfma_f32_16x16x32_bf16 v[116:119], v[158:161], v[178:181], v[116:119]
	s_waitcnt lgkmcnt(1)
	s_mov_b32 m0, s30
	v_mfma_f32_16x16x32_bf16 v[128:131], v[158:161], v[222:225], v[128:131]
	global_load_lds_dwordx4 v2, s[48:49]
	s_waitcnt lgkmcnt(0)
	v_mfma_f32_16x16x32_bf16 v[100:103], v[158:161], v[226:229], v[100:103]
	ds_read_b128 v[158:161], v20
	v_mfma_f32_16x16x32_bf16 v[108:111], v[166:169], v[162:165], v[108:111]
	v_mfma_f32_16x16x32_bf16 v[120:123], v[166:169], v[178:181], v[120:123]
	v_mfma_f32_16x16x32_bf16 v[132:135], v[166:169], v[222:225], v[132:135]
	s_mov_b32 m0, s31
	v_mfma_f32_16x16x32_bf16 v[140:143], v[166:169], v[226:229], v[140:143]
	global_load_lds_dwordx4 v4, s[46:47]
	ds_read_b128 v[166:169], v24
	v_mfma_f32_16x16x32_bf16 v[112:115], v[214:217], v[162:165], v[112:115]
	v_mfma_f32_16x16x32_bf16 v[52:55], v[218:221], v[162:165], v[52:55]
	ds_read_b128 v[162:165], v21
	v_mfma_f32_16x16x32_bf16 v[124:127], v[214:217], v[178:181], v[124:127]
	v_mfma_f32_16x16x32_bf16 v[68:71], v[218:221], v[178:181], v[68:71]
	ds_read_b128 v[178:181], v25
	s_mov_b32 m0, s34
	v_mfma_f32_16x16x32_bf16 v[136:139], v[214:217], v[222:225], v[136:139]
	global_load_lds_dwordx4 v4, s[48:49]
	v_mfma_f32_16x16x32_bf16 v[84:87], v[218:221], v[222:225], v[84:87]
	ds_read_b128 v[222:225], v26
	v_mfma_f32_16x16x32_bf16 v[150:153], v[214:217], v[226:229], v[150:153]
	ds_read_b128 v[214:217], v23
	v_mfma_f32_16x16x32_bf16 v[154:157], v[218:221], v[226:229], v[154:157]
	ds_read_b128 v[218:221], v22
	ds_read_b128 v[226:229], v27
	s_waitcnt lgkmcnt(6)
	v_mfma_f32_16x16x32_bf16 v[40:43], v[158:161], v[166:169], v[40:43]
	s_waitcnt lgkmcnt(5)
	s_mov_b32 m0, s35
	v_mfma_f32_16x16x32_bf16 v[44:47], v[162:165], v[166:169], v[44:47]
	global_load_lds_dwordx4 v146, s[46:47]
	s_waitcnt lgkmcnt(4)
	v_mfma_f32_16x16x32_bf16 v[56:59], v[158:161], v[178:181], v[56:59]
	v_mfma_f32_16x16x32_bf16 v[60:63], v[162:165], v[178:181], v[60:63]
	s_waitcnt lgkmcnt(3)
	v_mfma_f32_16x16x32_bf16 v[72:75], v[158:161], v[222:225], v[72:75]
	v_mfma_f32_16x16x32_bf16 v[76:79], v[162:165], v[222:225], v[76:79]
	s_waitcnt lgkmcnt(2)
	s_mov_b32 m0, s36
	v_mfma_f32_16x16x32_bf16 v[48:51], v[214:217], v[166:169], v[48:51]
	global_load_lds_dwordx4 v146, s[48:49]
	s_waitcnt lgkmcnt(1)
	v_mfma_f32_16x16x32_bf16 v[174:177], v[218:221], v[166:169], v[174:177]
	ds_read_b128 v[166:169], v28
	v_mfma_f32_16x16x32_bf16 v[64:67], v[214:217], v[178:181], v[64:67]
	v_mfma_f32_16x16x32_bf16 v[170:173], v[218:221], v[178:181], v[170:173]
	ds_read_b128 v[178:181], v29
	v_mfma_f32_16x16x32_bf16 v[80:83], v[214:217], v[222:225], v[80:83]
	v_mfma_f32_16x16x32_bf16 v[32:35], v[218:221], v[222:225], v[32:35]
	ds_read_b128 v[222:225], v30
	s_waitcnt lgkmcnt(3)
	v_mfma_f32_16x16x32_bf16 v[88:91], v[158:161], v[226:229], v[88:91]
	v_mfma_f32_16x16x32_bf16 v[92:95], v[162:165], v[226:229], v[92:95]
	v_mfma_f32_16x16x32_bf16 v[96:99], v[214:217], v[226:229], v[96:99]
	v_mfma_f32_16x16x32_bf16 v[36:39], v[218:221], v[226:229], v[36:39]
	ds_read_b128 v[226:229], v31
	s_waitcnt lgkmcnt(3)
	v_mfma_f32_16x16x32_bf16 v[104:107], v[158:161], v[166:169], v[104:107]
	v_mfma_f32_16x16x32_bf16 v[108:111], v[162:165], v[166:169], v[108:111]
	v_mfma_f32_16x16x32_bf16 v[112:115], v[214:217], v[166:169], v[112:115]
	v_mfma_f32_16x16x32_bf16 v[52:55], v[218:221], v[166:169], v[52:55]
	s_waitcnt lgkmcnt(2)
	v_mfma_f32_16x16x32_bf16 v[116:119], v[158:161], v[178:181], v[116:119]
	v_mfma_f32_16x16x32_bf16 v[120:123], v[162:165], v[178:181], v[120:123]
	v_mfma_f32_16x16x32_bf16 v[124:127], v[214:217], v[178:181], v[124:127]
	v_mfma_f32_16x16x32_bf16 v[68:71], v[218:221], v[178:181], v[68:71]
	s_waitcnt lgkmcnt(1)
	v_mfma_f32_16x16x32_bf16 v[128:131], v[158:161], v[222:225], v[128:131]
	v_mfma_f32_16x16x32_bf16 v[132:135], v[162:165], v[222:225], v[132:135]
	v_mfma_f32_16x16x32_bf16 v[136:139], v[214:217], v[222:225], v[136:139]
	v_mfma_f32_16x16x32_bf16 v[84:87], v[218:221], v[222:225], v[84:87]
	s_waitcnt lgkmcnt(0)
	v_mfma_f32_16x16x32_bf16 v[100:103], v[158:161], v[226:229], v[100:103]
	v_mfma_f32_16x16x32_bf16 v[140:143], v[162:165], v[226:229], v[140:143]
	v_mfma_f32_16x16x32_bf16 v[150:153], v[214:217], v[226:229], v[150:153]
	v_mfma_f32_16x16x32_bf16 v[154:157], v[218:221], v[226:229], v[154:157]
	s_add_u32 s46, s0, 0x1980
	s_addc_u32 s47, s1, 0
	s_add_u32 s48, s14, 0x1980
	s_waitcnt vmcnt(0)
	s_barrier
	s_addc_u32 s49, s15, 0
	ds_read_b128 v[158:161], v7 offset:32768
	ds_read_b128 v[162:165], v6
	ds_read_b128 v[166:169], v7 offset:34816
	ds_read_b128 v[178:181], v6 offset:2048
	ds_read_b128 v[214:217], v7 offset:36864
	ds_read_b128 v[218:221], v7 offset:38912
	ds_read_b128 v[222:225], v6 offset:4096
	ds_read_b128 v[226:229], v6 offset:6144
	s_waitcnt lgkmcnt(6)
	v_mfma_f32_16x16x32_bf16 v[40:43], v[158:161], v[162:165], v[40:43]
	s_waitcnt lgkmcnt(5)
	v_mfma_f32_16x16x32_bf16 v[44:47], v[166:169], v[162:165], v[44:47]
	s_waitcnt lgkmcnt(4)
	v_mfma_f32_16x16x32_bf16 v[56:59], v[158:161], v[178:181], v[56:59]
	s_mov_b32 m0, s38
	v_mfma_f32_16x16x32_bf16 v[60:63], v[166:169], v[178:181], v[60:63]
	global_load_lds_dwordx4 v0, s[46:47]
	s_waitcnt lgkmcnt(3)
	v_mfma_f32_16x16x32_bf16 v[48:51], v[214:217], v[162:165], v[48:51]
	v_mfma_f32_16x16x32_bf16 v[64:67], v[214:217], v[178:181], v[64:67]
	s_waitcnt lgkmcnt(2)
	v_mfma_f32_16x16x32_bf16 v[174:177], v[218:221], v[162:165], v[174:177]
	ds_read_b128 v[162:165], v6 offset:8192
	v_mfma_f32_16x16x32_bf16 v[170:173], v[218:221], v[178:181], v[170:173]
	ds_read_b128 v[178:181], v6 offset:10240
	s_waitcnt lgkmcnt(3)
	s_mov_b32 m0, s37
	v_mfma_f32_16x16x32_bf16 v[72:75], v[158:161], v[222:225], v[72:75]
	global_load_lds_dwordx4 v0, s[48:49]
	v_mfma_f32_16x16x32_bf16 v[76:79], v[166:169], v[222:225], v[76:79]
	v_mfma_f32_16x16x32_bf16 v[80:83], v[214:217], v[222:225], v[80:83]
	v_mfma_f32_16x16x32_bf16 v[32:35], v[218:221], v[222:225], v[32:35]
	ds_read_b128 v[222:225], v6 offset:12288
	s_waitcnt lgkmcnt(3)
	v_mfma_f32_16x16x32_bf16 v[88:91], v[158:161], v[226:229], v[88:91]
	s_mov_b32 m0, s39
	v_mfma_f32_16x16x32_bf16 v[92:95], v[166:169], v[226:229], v[92:95]
	global_load_lds_dwordx4 v2, s[46:47]
	v_mfma_f32_16x16x32_bf16 v[96:99], v[214:217], v[226:229], v[96:99]
	v_mfma_f32_16x16x32_bf16 v[36:39], v[218:221], v[226:229], v[36:39]
	ds_read_b128 v[226:229], v6 offset:14336
	s_waitcnt lgkmcnt(3)
	v_mfma_f32_16x16x32_bf16 v[104:107], v[158:161], v[162:165], v[104:107]
	s_waitcnt lgkmcnt(2)
	v_mfma_f32_16x16x32_bf16 v[116:119], v[158:161], v[178:181], v[116:119]
	s_waitcnt lgkmcnt(1)
	s_mov_b32 m0, s40
	v_mfma_f32_16x16x32_bf16 v[128:131], v[158:161], v[222:225], v[128:131]
	global_load_lds_dwordx4 v2, s[48:49]
	s_waitcnt lgkmcnt(0)
	v_mfma_f32_16x16x32_bf16 v[100:103], v[158:161], v[226:229], v[100:103]
	ds_read_b128 v[158:161], v7 offset:33792
	v_mfma_f32_16x16x32_bf16 v[108:111], v[166:169], v[162:165], v[108:111]
	v_mfma_f32_16x16x32_bf16 v[120:123], v[166:169], v[178:181], v[120:123]
	v_mfma_f32_16x16x32_bf16 v[132:135], v[166:169], v[222:225], v[132:135]
	s_mov_b32 m0, s41
	v_mfma_f32_16x16x32_bf16 v[140:143], v[166:169], v[226:229], v[140:143]
	global_load_lds_dwordx4 v4, s[46:47]
	ds_read_b128 v[166:169], v6 offset:1024
	v_mfma_f32_16x16x32_bf16 v[112:115], v[214:217], v[162:165], v[112:115]
	v_mfma_f32_16x16x32_bf16 v[52:55], v[218:221], v[162:165], v[52:55]
	ds_read_b128 v[162:165], v7 offset:35840
	v_mfma_f32_16x16x32_bf16 v[124:127], v[214:217], v[178:181], v[124:127]
	v_mfma_f32_16x16x32_bf16 v[68:71], v[218:221], v[178:181], v[68:71]
	ds_read_b128 v[178:181], v6 offset:3072
	s_mov_b32 m0, s42
	v_mfma_f32_16x16x32_bf16 v[136:139], v[214:217], v[222:225], v[136:139]
	global_load_lds_dwordx4 v4, s[48:49]
	v_mfma_f32_16x16x32_bf16 v[84:87], v[218:221], v[222:225], v[84:87]
	ds_read_b128 v[222:225], v6 offset:5120
	v_mfma_f32_16x16x32_bf16 v[150:153], v[214:217], v[226:229], v[150:153]
	ds_read_b128 v[214:217], v7 offset:37888
	v_mfma_f32_16x16x32_bf16 v[154:157], v[218:221], v[226:229], v[154:157]
	ds_read_b128 v[218:221], v7 offset:39936
	ds_read_b128 v[226:229], v6 offset:7168
	s_waitcnt lgkmcnt(6)
	v_mfma_f32_16x16x32_bf16 v[40:43], v[158:161], v[166:169], v[40:43]
	s_waitcnt lgkmcnt(5)
	s_mov_b32 m0, s43
	v_mfma_f32_16x16x32_bf16 v[44:47], v[162:165], v[166:169], v[44:47]
	global_load_lds_dwordx4 v146, s[46:47]
	s_waitcnt lgkmcnt(4)
	v_mfma_f32_16x16x32_bf16 v[56:59], v[158:161], v[178:181], v[56:59]
	v_mfma_f32_16x16x32_bf16 v[60:63], v[162:165], v[178:181], v[60:63]
	s_waitcnt lgkmcnt(3)
	v_mfma_f32_16x16x32_bf16 v[72:75], v[158:161], v[222:225], v[72:75]
	v_mfma_f32_16x16x32_bf16 v[76:79], v[162:165], v[222:225], v[76:79]
	s_waitcnt lgkmcnt(2)
	s_mov_b32 m0, s44
	v_mfma_f32_16x16x32_bf16 v[48:51], v[214:217], v[166:169], v[48:51]
	global_load_lds_dwordx4 v146, s[48:49]
	s_waitcnt lgkmcnt(1)
	v_mfma_f32_16x16x32_bf16 v[174:177], v[218:221], v[166:169], v[174:177]
	ds_read_b128 v[166:169], v6 offset:9216
	v_mfma_f32_16x16x32_bf16 v[64:67], v[214:217], v[178:181], v[64:67]
	v_mfma_f32_16x16x32_bf16 v[170:173], v[218:221], v[178:181], v[170:173]
	ds_read_b128 v[178:181], v6 offset:11264
	v_mfma_f32_16x16x32_bf16 v[80:83], v[214:217], v[222:225], v[80:83]
	v_mfma_f32_16x16x32_bf16 v[32:35], v[218:221], v[222:225], v[32:35]
	ds_read_b128 v[222:225], v6 offset:13312
	s_waitcnt lgkmcnt(3)
	v_mfma_f32_16x16x32_bf16 v[88:91], v[158:161], v[226:229], v[88:91]
	v_mfma_f32_16x16x32_bf16 v[92:95], v[162:165], v[226:229], v[92:95]
	v_mfma_f32_16x16x32_bf16 v[96:99], v[214:217], v[226:229], v[96:99]
	v_mfma_f32_16x16x32_bf16 v[36:39], v[218:221], v[226:229], v[36:39]
	ds_read_b128 v[226:229], v6 offset:15360
	s_waitcnt lgkmcnt(3)
	v_mfma_f32_16x16x32_bf16 v[104:107], v[158:161], v[166:169], v[104:107]
	v_mfma_f32_16x16x32_bf16 v[108:111], v[162:165], v[166:169], v[108:111]
	v_mfma_f32_16x16x32_bf16 v[112:115], v[214:217], v[166:169], v[112:115]
	v_mfma_f32_16x16x32_bf16 v[52:55], v[218:221], v[166:169], v[52:55]
	s_waitcnt lgkmcnt(2)
	v_mfma_f32_16x16x32_bf16 v[116:119], v[158:161], v[178:181], v[116:119]
	v_mfma_f32_16x16x32_bf16 v[120:123], v[162:165], v[178:181], v[120:123]
	v_mfma_f32_16x16x32_bf16 v[124:127], v[214:217], v[178:181], v[124:127]
	v_mfma_f32_16x16x32_bf16 v[68:71], v[218:221], v[178:181], v[68:71]
	s_waitcnt lgkmcnt(1)
	v_mfma_f32_16x16x32_bf16 v[128:131], v[158:161], v[222:225], v[128:131]
	v_mfma_f32_16x16x32_bf16 v[132:135], v[162:165], v[222:225], v[132:135]
	v_mfma_f32_16x16x32_bf16 v[136:139], v[214:217], v[222:225], v[136:139]
	v_mfma_f32_16x16x32_bf16 v[84:87], v[218:221], v[222:225], v[84:87]
	s_waitcnt lgkmcnt(0)
	v_mfma_f32_16x16x32_bf16 v[100:103], v[158:161], v[226:229], v[100:103]
	v_mfma_f32_16x16x32_bf16 v[140:143], v[162:165], v[226:229], v[140:143]
	v_mfma_f32_16x16x32_bf16 v[150:153], v[214:217], v[226:229], v[150:153]
	v_mfma_f32_16x16x32_bf16 v[154:157], v[218:221], v[226:229], v[154:157]
	s_add_u32 s46, s0, 0x1a00
	s_addc_u32 s47, s1, 0
	s_add_u32 s48, s14, 0x1a00
	s_waitcnt vmcnt(0)
	s_barrier
	s_addc_u32 s49, s15, 0
	ds_read_b128 v[158:161], v8
	ds_read_b128 v[162:165], v12
	ds_read_b128 v[166:169], v9
	ds_read_b128 v[178:181], v13
	ds_read_b128 v[214:217], v11
	ds_read_b128 v[218:221], v10
	ds_read_b128 v[222:225], v14
	ds_read_b128 v[226:229], v15
	s_waitcnt lgkmcnt(6)
	v_mfma_f32_16x16x32_bf16 v[40:43], v[158:161], v[162:165], v[40:43]
	s_waitcnt lgkmcnt(5)
	v_mfma_f32_16x16x32_bf16 v[44:47], v[166:169], v[162:165], v[44:47]
	s_waitcnt lgkmcnt(4)
	v_mfma_f32_16x16x32_bf16 v[56:59], v[158:161], v[178:181], v[56:59]
	s_mov_b32 m0, s27
	v_mfma_f32_16x16x32_bf16 v[60:63], v[166:169], v[178:181], v[60:63]
	global_load_lds_dwordx4 v0, s[46:47]
	s_waitcnt lgkmcnt(3)
	v_mfma_f32_16x16x32_bf16 v[48:51], v[214:217], v[162:165], v[48:51]
	v_mfma_f32_16x16x32_bf16 v[64:67], v[214:217], v[178:181], v[64:67]
	s_waitcnt lgkmcnt(2)
	v_mfma_f32_16x16x32_bf16 v[174:177], v[218:221], v[162:165], v[174:177]
	ds_read_b128 v[162:165], v16
	v_mfma_f32_16x16x32_bf16 v[170:173], v[218:221], v[178:181], v[170:173]
	ds_read_b128 v[178:181], v17
	s_waitcnt lgkmcnt(3)
	s_mov_b32 m0, s28
	v_mfma_f32_16x16x32_bf16 v[72:75], v[158:161], v[222:225], v[72:75]
	global_load_lds_dwordx4 v0, s[48:49]
	v_mfma_f32_16x16x32_bf16 v[76:79], v[166:169], v[222:225], v[76:79]
	v_mfma_f32_16x16x32_bf16 v[80:83], v[214:217], v[222:225], v[80:83]
	v_mfma_f32_16x16x32_bf16 v[32:35], v[218:221], v[222:225], v[32:35]
	ds_read_b128 v[222:225], v18
	s_waitcnt lgkmcnt(3)
	v_mfma_f32_16x16x32_bf16 v[88:91], v[158:161], v[226:229], v[88:91]
	s_mov_b32 m0, s29
	v_mfma_f32_16x16x32_bf16 v[92:95], v[166:169], v[226:229], v[92:95]
	global_load_lds_dwordx4 v2, s[46:47]
	v_mfma_f32_16x16x32_bf16 v[96:99], v[214:217], v[226:229], v[96:99]
	v_mfma_f32_16x16x32_bf16 v[36:39], v[218:221], v[226:229], v[36:39]
	ds_read_b128 v[226:229], v19
	s_waitcnt lgkmcnt(3)
	v_mfma_f32_16x16x32_bf16 v[104:107], v[158:161], v[162:165], v[104:107]
	s_waitcnt lgkmcnt(2)
	v_mfma_f32_16x16x32_bf16 v[116:119], v[158:161], v[178:181], v[116:119]
	s_waitcnt lgkmcnt(1)
	s_mov_b32 m0, s30
	v_mfma_f32_16x16x32_bf16 v[128:131], v[158:161], v[222:225], v[128:131]
	global_load_lds_dwordx4 v2, s[48:49]
	s_waitcnt lgkmcnt(0)
	v_mfma_f32_16x16x32_bf16 v[100:103], v[158:161], v[226:229], v[100:103]
	ds_read_b128 v[158:161], v20
	v_mfma_f32_16x16x32_bf16 v[108:111], v[166:169], v[162:165], v[108:111]
	v_mfma_f32_16x16x32_bf16 v[120:123], v[166:169], v[178:181], v[120:123]
	v_mfma_f32_16x16x32_bf16 v[132:135], v[166:169], v[222:225], v[132:135]
	s_mov_b32 m0, s31
	v_mfma_f32_16x16x32_bf16 v[140:143], v[166:169], v[226:229], v[140:143]
	global_load_lds_dwordx4 v4, s[46:47]
	ds_read_b128 v[166:169], v24
	v_mfma_f32_16x16x32_bf16 v[112:115], v[214:217], v[162:165], v[112:115]
	v_mfma_f32_16x16x32_bf16 v[52:55], v[218:221], v[162:165], v[52:55]
	ds_read_b128 v[162:165], v21
	v_mfma_f32_16x16x32_bf16 v[124:127], v[214:217], v[178:181], v[124:127]
	v_mfma_f32_16x16x32_bf16 v[68:71], v[218:221], v[178:181], v[68:71]
	ds_read_b128 v[178:181], v25
	s_mov_b32 m0, s34
	v_mfma_f32_16x16x32_bf16 v[136:139], v[214:217], v[222:225], v[136:139]
	global_load_lds_dwordx4 v4, s[48:49]
	v_mfma_f32_16x16x32_bf16 v[84:87], v[218:221], v[222:225], v[84:87]
	ds_read_b128 v[222:225], v26
	v_mfma_f32_16x16x32_bf16 v[150:153], v[214:217], v[226:229], v[150:153]
	ds_read_b128 v[214:217], v23
	v_mfma_f32_16x16x32_bf16 v[154:157], v[218:221], v[226:229], v[154:157]
	ds_read_b128 v[218:221], v22
	ds_read_b128 v[226:229], v27
	s_waitcnt lgkmcnt(6)
	v_mfma_f32_16x16x32_bf16 v[40:43], v[158:161], v[166:169], v[40:43]
	s_waitcnt lgkmcnt(5)
	s_mov_b32 m0, s35
	v_mfma_f32_16x16x32_bf16 v[44:47], v[162:165], v[166:169], v[44:47]
	global_load_lds_dwordx4 v146, s[46:47]
	s_waitcnt lgkmcnt(4)
	v_mfma_f32_16x16x32_bf16 v[56:59], v[158:161], v[178:181], v[56:59]
	v_mfma_f32_16x16x32_bf16 v[60:63], v[162:165], v[178:181], v[60:63]
	s_waitcnt lgkmcnt(3)
	v_mfma_f32_16x16x32_bf16 v[72:75], v[158:161], v[222:225], v[72:75]
	v_mfma_f32_16x16x32_bf16 v[76:79], v[162:165], v[222:225], v[76:79]
	s_waitcnt lgkmcnt(2)
	s_mov_b32 m0, s36
	v_mfma_f32_16x16x32_bf16 v[48:51], v[214:217], v[166:169], v[48:51]
	global_load_lds_dwordx4 v146, s[48:49]
	s_waitcnt lgkmcnt(1)
	v_mfma_f32_16x16x32_bf16 v[174:177], v[218:221], v[166:169], v[174:177]
	ds_read_b128 v[166:169], v28
	v_mfma_f32_16x16x32_bf16 v[64:67], v[214:217], v[178:181], v[64:67]
	v_mfma_f32_16x16x32_bf16 v[170:173], v[218:221], v[178:181], v[170:173]
	ds_read_b128 v[178:181], v29
	v_mfma_f32_16x16x32_bf16 v[80:83], v[214:217], v[222:225], v[80:83]
	v_mfma_f32_16x16x32_bf16 v[32:35], v[218:221], v[222:225], v[32:35]
	ds_read_b128 v[222:225], v30
	s_waitcnt lgkmcnt(3)
	v_mfma_f32_16x16x32_bf16 v[88:91], v[158:161], v[226:229], v[88:91]
	v_mfma_f32_16x16x32_bf16 v[92:95], v[162:165], v[226:229], v[92:95]
	v_mfma_f32_16x16x32_bf16 v[96:99], v[214:217], v[226:229], v[96:99]
	v_mfma_f32_16x16x32_bf16 v[36:39], v[218:221], v[226:229], v[36:39]
	ds_read_b128 v[226:229], v31
	s_waitcnt lgkmcnt(3)
	v_mfma_f32_16x16x32_bf16 v[104:107], v[158:161], v[166:169], v[104:107]
	v_mfma_f32_16x16x32_bf16 v[108:111], v[162:165], v[166:169], v[108:111]
	v_mfma_f32_16x16x32_bf16 v[112:115], v[214:217], v[166:169], v[112:115]
	v_mfma_f32_16x16x32_bf16 v[52:55], v[218:221], v[166:169], v[52:55]
	s_waitcnt lgkmcnt(2)
	v_mfma_f32_16x16x32_bf16 v[116:119], v[158:161], v[178:181], v[116:119]
	v_mfma_f32_16x16x32_bf16 v[120:123], v[162:165], v[178:181], v[120:123]
	v_mfma_f32_16x16x32_bf16 v[124:127], v[214:217], v[178:181], v[124:127]
	v_mfma_f32_16x16x32_bf16 v[68:71], v[218:221], v[178:181], v[68:71]
	s_waitcnt lgkmcnt(1)
	v_mfma_f32_16x16x32_bf16 v[128:131], v[158:161], v[222:225], v[128:131]
	v_mfma_f32_16x16x32_bf16 v[132:135], v[162:165], v[222:225], v[132:135]
	v_mfma_f32_16x16x32_bf16 v[136:139], v[214:217], v[222:225], v[136:139]
	v_mfma_f32_16x16x32_bf16 v[84:87], v[218:221], v[222:225], v[84:87]
	s_waitcnt lgkmcnt(0)
	v_mfma_f32_16x16x32_bf16 v[100:103], v[158:161], v[226:229], v[100:103]
	v_mfma_f32_16x16x32_bf16 v[140:143], v[162:165], v[226:229], v[140:143]
	v_mfma_f32_16x16x32_bf16 v[150:153], v[214:217], v[226:229], v[150:153]
	v_mfma_f32_16x16x32_bf16 v[154:157], v[218:221], v[226:229], v[154:157]
	s_add_u32 s46, s0, 0x1a80
	s_addc_u32 s47, s1, 0
	s_add_u32 s48, s14, 0x1a80
	s_waitcnt vmcnt(0)
	s_barrier
	s_addc_u32 s49, s15, 0
	ds_read_b128 v[158:161], v7 offset:32768
	ds_read_b128 v[162:165], v6
	ds_read_b128 v[166:169], v7 offset:34816
	ds_read_b128 v[178:181], v6 offset:2048
	ds_read_b128 v[214:217], v7 offset:36864
	ds_read_b128 v[218:221], v7 offset:38912
	ds_read_b128 v[222:225], v6 offset:4096
	ds_read_b128 v[226:229], v6 offset:6144
	s_waitcnt lgkmcnt(6)
	v_mfma_f32_16x16x32_bf16 v[40:43], v[158:161], v[162:165], v[40:43]
	s_waitcnt lgkmcnt(5)
	v_mfma_f32_16x16x32_bf16 v[44:47], v[166:169], v[162:165], v[44:47]
	s_waitcnt lgkmcnt(4)
	v_mfma_f32_16x16x32_bf16 v[56:59], v[158:161], v[178:181], v[56:59]
	s_mov_b32 m0, s38
	v_mfma_f32_16x16x32_bf16 v[60:63], v[166:169], v[178:181], v[60:63]
	global_load_lds_dwordx4 v0, s[46:47]
	s_waitcnt lgkmcnt(3)
	v_mfma_f32_16x16x32_bf16 v[48:51], v[214:217], v[162:165], v[48:51]
	v_mfma_f32_16x16x32_bf16 v[64:67], v[214:217], v[178:181], v[64:67]
	s_waitcnt lgkmcnt(2)
	v_mfma_f32_16x16x32_bf16 v[174:177], v[218:221], v[162:165], v[174:177]
	ds_read_b128 v[162:165], v6 offset:8192
	v_mfma_f32_16x16x32_bf16 v[170:173], v[218:221], v[178:181], v[170:173]
	ds_read_b128 v[178:181], v6 offset:10240
	s_waitcnt lgkmcnt(3)
	s_mov_b32 m0, s37
	v_mfma_f32_16x16x32_bf16 v[72:75], v[158:161], v[222:225], v[72:75]
	global_load_lds_dwordx4 v0, s[48:49]
	v_mfma_f32_16x16x32_bf16 v[76:79], v[166:169], v[222:225], v[76:79]
	v_mfma_f32_16x16x32_bf16 v[80:83], v[214:217], v[222:225], v[80:83]
	v_mfma_f32_16x16x32_bf16 v[32:35], v[218:221], v[222:225], v[32:35]
	ds_read_b128 v[222:225], v6 offset:12288
	s_waitcnt lgkmcnt(3)
	v_mfma_f32_16x16x32_bf16 v[88:91], v[158:161], v[226:229], v[88:91]
	s_mov_b32 m0, s39
	v_mfma_f32_16x16x32_bf16 v[92:95], v[166:169], v[226:229], v[92:95]
	global_load_lds_dwordx4 v2, s[46:47]
	v_mfma_f32_16x16x32_bf16 v[96:99], v[214:217], v[226:229], v[96:99]
	v_mfma_f32_16x16x32_bf16 v[36:39], v[218:221], v[226:229], v[36:39]
	ds_read_b128 v[226:229], v6 offset:14336
	s_waitcnt lgkmcnt(3)
	v_mfma_f32_16x16x32_bf16 v[104:107], v[158:161], v[162:165], v[104:107]
	s_waitcnt lgkmcnt(2)
	v_mfma_f32_16x16x32_bf16 v[116:119], v[158:161], v[178:181], v[116:119]
	s_waitcnt lgkmcnt(1)
	s_mov_b32 m0, s40
	v_mfma_f32_16x16x32_bf16 v[128:131], v[158:161], v[222:225], v[128:131]
	global_load_lds_dwordx4 v2, s[48:49]
	s_waitcnt lgkmcnt(0)
	v_mfma_f32_16x16x32_bf16 v[100:103], v[158:161], v[226:229], v[100:103]
	ds_read_b128 v[158:161], v7 offset:33792
	v_mfma_f32_16x16x32_bf16 v[108:111], v[166:169], v[162:165], v[108:111]
	v_mfma_f32_16x16x32_bf16 v[120:123], v[166:169], v[178:181], v[120:123]
	v_mfma_f32_16x16x32_bf16 v[132:135], v[166:169], v[222:225], v[132:135]
	s_mov_b32 m0, s41
	v_mfma_f32_16x16x32_bf16 v[140:143], v[166:169], v[226:229], v[140:143]
	global_load_lds_dwordx4 v4, s[46:47]
	ds_read_b128 v[166:169], v6 offset:1024
	v_mfma_f32_16x16x32_bf16 v[112:115], v[214:217], v[162:165], v[112:115]
	v_mfma_f32_16x16x32_bf16 v[52:55], v[218:221], v[162:165], v[52:55]
	ds_read_b128 v[162:165], v7 offset:35840
	v_mfma_f32_16x16x32_bf16 v[124:127], v[214:217], v[178:181], v[124:127]
	v_mfma_f32_16x16x32_bf16 v[68:71], v[218:221], v[178:181], v[68:71]
	ds_read_b128 v[178:181], v6 offset:3072
	s_mov_b32 m0, s42
	v_mfma_f32_16x16x32_bf16 v[136:139], v[214:217], v[222:225], v[136:139]
	global_load_lds_dwordx4 v4, s[48:49]
	v_mfma_f32_16x16x32_bf16 v[84:87], v[218:221], v[222:225], v[84:87]
	ds_read_b128 v[222:225], v6 offset:5120
	v_mfma_f32_16x16x32_bf16 v[150:153], v[214:217], v[226:229], v[150:153]
	ds_read_b128 v[214:217], v7 offset:37888
	v_mfma_f32_16x16x32_bf16 v[154:157], v[218:221], v[226:229], v[154:157]
	ds_read_b128 v[218:221], v7 offset:39936
	ds_read_b128 v[226:229], v6 offset:7168
	s_waitcnt lgkmcnt(6)
	v_mfma_f32_16x16x32_bf16 v[40:43], v[158:161], v[166:169], v[40:43]
	s_waitcnt lgkmcnt(5)
	s_mov_b32 m0, s43
	v_mfma_f32_16x16x32_bf16 v[44:47], v[162:165], v[166:169], v[44:47]
	global_load_lds_dwordx4 v146, s[46:47]
	s_waitcnt lgkmcnt(4)
	v_mfma_f32_16x16x32_bf16 v[56:59], v[158:161], v[178:181], v[56:59]
	v_mfma_f32_16x16x32_bf16 v[60:63], v[162:165], v[178:181], v[60:63]
	s_waitcnt lgkmcnt(3)
	v_mfma_f32_16x16x32_bf16 v[72:75], v[158:161], v[222:225], v[72:75]
	v_mfma_f32_16x16x32_bf16 v[76:79], v[162:165], v[222:225], v[76:79]
	s_waitcnt lgkmcnt(2)
	s_mov_b32 m0, s44
	v_mfma_f32_16x16x32_bf16 v[48:51], v[214:217], v[166:169], v[48:51]
	global_load_lds_dwordx4 v146, s[48:49]
	s_waitcnt lgkmcnt(1)
	v_mfma_f32_16x16x32_bf16 v[174:177], v[218:221], v[166:169], v[174:177]
	ds_read_b128 v[166:169], v6 offset:9216
	v_mfma_f32_16x16x32_bf16 v[64:67], v[214:217], v[178:181], v[64:67]
	v_mfma_f32_16x16x32_bf16 v[170:173], v[218:221], v[178:181], v[170:173]
	ds_read_b128 v[178:181], v6 offset:11264
	v_mfma_f32_16x16x32_bf16 v[80:83], v[214:217], v[222:225], v[80:83]
	v_mfma_f32_16x16x32_bf16 v[32:35], v[218:221], v[222:225], v[32:35]
	ds_read_b128 v[222:225], v6 offset:13312
	s_waitcnt lgkmcnt(3)
	v_mfma_f32_16x16x32_bf16 v[88:91], v[158:161], v[226:229], v[88:91]
	v_mfma_f32_16x16x32_bf16 v[92:95], v[162:165], v[226:229], v[92:95]
	v_mfma_f32_16x16x32_bf16 v[96:99], v[214:217], v[226:229], v[96:99]
	v_mfma_f32_16x16x32_bf16 v[36:39], v[218:221], v[226:229], v[36:39]
	ds_read_b128 v[226:229], v6 offset:15360
	s_waitcnt lgkmcnt(3)
	v_mfma_f32_16x16x32_bf16 v[104:107], v[158:161], v[166:169], v[104:107]
	v_mfma_f32_16x16x32_bf16 v[108:111], v[162:165], v[166:169], v[108:111]
	v_mfma_f32_16x16x32_bf16 v[112:115], v[214:217], v[166:169], v[112:115]
	v_mfma_f32_16x16x32_bf16 v[52:55], v[218:221], v[166:169], v[52:55]
	s_waitcnt lgkmcnt(2)
	v_mfma_f32_16x16x32_bf16 v[116:119], v[158:161], v[178:181], v[116:119]
	v_mfma_f32_16x16x32_bf16 v[120:123], v[162:165], v[178:181], v[120:123]
	v_mfma_f32_16x16x32_bf16 v[124:127], v[214:217], v[178:181], v[124:127]
	v_mfma_f32_16x16x32_bf16 v[68:71], v[218:221], v[178:181], v[68:71]
	s_waitcnt lgkmcnt(1)
	v_mfma_f32_16x16x32_bf16 v[128:131], v[158:161], v[222:225], v[128:131]
	v_mfma_f32_16x16x32_bf16 v[132:135], v[162:165], v[222:225], v[132:135]
	v_mfma_f32_16x16x32_bf16 v[136:139], v[214:217], v[222:225], v[136:139]
	v_mfma_f32_16x16x32_bf16 v[84:87], v[218:221], v[222:225], v[84:87]
	s_waitcnt lgkmcnt(0)
	v_mfma_f32_16x16x32_bf16 v[100:103], v[158:161], v[226:229], v[100:103]
	v_mfma_f32_16x16x32_bf16 v[140:143], v[162:165], v[226:229], v[140:143]
	v_mfma_f32_16x16x32_bf16 v[150:153], v[214:217], v[226:229], v[150:153]
	v_mfma_f32_16x16x32_bf16 v[154:157], v[218:221], v[226:229], v[154:157]
	s_add_u32 s46, s0, 0x1b00
	s_addc_u32 s47, s1, 0
	s_add_u32 s48, s14, 0x1b00
	s_waitcnt vmcnt(0)
	s_barrier
	s_addc_u32 s49, s15, 0
	ds_read_b128 v[158:161], v8
	ds_read_b128 v[162:165], v12
	ds_read_b128 v[166:169], v9
	ds_read_b128 v[178:181], v13
	ds_read_b128 v[214:217], v11
	ds_read_b128 v[218:221], v10
	ds_read_b128 v[222:225], v14
	ds_read_b128 v[226:229], v15
	s_waitcnt lgkmcnt(6)
	v_mfma_f32_16x16x32_bf16 v[40:43], v[158:161], v[162:165], v[40:43]
	s_waitcnt lgkmcnt(5)
	v_mfma_f32_16x16x32_bf16 v[44:47], v[166:169], v[162:165], v[44:47]
	s_waitcnt lgkmcnt(4)
	v_mfma_f32_16x16x32_bf16 v[56:59], v[158:161], v[178:181], v[56:59]
	s_mov_b32 m0, s27
	v_mfma_f32_16x16x32_bf16 v[60:63], v[166:169], v[178:181], v[60:63]
	global_load_lds_dwordx4 v0, s[46:47]
	s_waitcnt lgkmcnt(3)
	v_mfma_f32_16x16x32_bf16 v[48:51], v[214:217], v[162:165], v[48:51]
	v_mfma_f32_16x16x32_bf16 v[64:67], v[214:217], v[178:181], v[64:67]
	s_waitcnt lgkmcnt(2)
	v_mfma_f32_16x16x32_bf16 v[174:177], v[218:221], v[162:165], v[174:177]
	ds_read_b128 v[162:165], v16
	v_mfma_f32_16x16x32_bf16 v[170:173], v[218:221], v[178:181], v[170:173]
	ds_read_b128 v[178:181], v17
	s_waitcnt lgkmcnt(3)
	s_mov_b32 m0, s28
	v_mfma_f32_16x16x32_bf16 v[72:75], v[158:161], v[222:225], v[72:75]
	global_load_lds_dwordx4 v0, s[48:49]
	v_mfma_f32_16x16x32_bf16 v[76:79], v[166:169], v[222:225], v[76:79]
	v_mfma_f32_16x16x32_bf16 v[80:83], v[214:217], v[222:225], v[80:83]
	v_mfma_f32_16x16x32_bf16 v[32:35], v[218:221], v[222:225], v[32:35]
	ds_read_b128 v[222:225], v18
	s_waitcnt lgkmcnt(3)
	v_mfma_f32_16x16x32_bf16 v[88:91], v[158:161], v[226:229], v[88:91]
	s_mov_b32 m0, s29
	v_mfma_f32_16x16x32_bf16 v[92:95], v[166:169], v[226:229], v[92:95]
	global_load_lds_dwordx4 v2, s[46:47]
	v_mfma_f32_16x16x32_bf16 v[96:99], v[214:217], v[226:229], v[96:99]
	v_mfma_f32_16x16x32_bf16 v[36:39], v[218:221], v[226:229], v[36:39]
	ds_read_b128 v[226:229], v19
	s_waitcnt lgkmcnt(3)
	v_mfma_f32_16x16x32_bf16 v[104:107], v[158:161], v[162:165], v[104:107]
	s_waitcnt lgkmcnt(2)
	v_mfma_f32_16x16x32_bf16 v[116:119], v[158:161], v[178:181], v[116:119]
	s_waitcnt lgkmcnt(1)
	s_mov_b32 m0, s30
	v_mfma_f32_16x16x32_bf16 v[128:131], v[158:161], v[222:225], v[128:131]
	global_load_lds_dwordx4 v2, s[48:49]
	s_waitcnt lgkmcnt(0)
	v_mfma_f32_16x16x32_bf16 v[100:103], v[158:161], v[226:229], v[100:103]
	ds_read_b128 v[158:161], v20
	v_mfma_f32_16x16x32_bf16 v[108:111], v[166:169], v[162:165], v[108:111]
	v_mfma_f32_16x16x32_bf16 v[120:123], v[166:169], v[178:181], v[120:123]
	v_mfma_f32_16x16x32_bf16 v[132:135], v[166:169], v[222:225], v[132:135]
	s_mov_b32 m0, s31
	v_mfma_f32_16x16x32_bf16 v[140:143], v[166:169], v[226:229], v[140:143]
	global_load_lds_dwordx4 v4, s[46:47]
	ds_read_b128 v[166:169], v24
	v_mfma_f32_16x16x32_bf16 v[112:115], v[214:217], v[162:165], v[112:115]
	v_mfma_f32_16x16x32_bf16 v[52:55], v[218:221], v[162:165], v[52:55]
	ds_read_b128 v[162:165], v21
	v_mfma_f32_16x16x32_bf16 v[124:127], v[214:217], v[178:181], v[124:127]
	v_mfma_f32_16x16x32_bf16 v[68:71], v[218:221], v[178:181], v[68:71]
	ds_read_b128 v[178:181], v25
	s_mov_b32 m0, s34
	v_mfma_f32_16x16x32_bf16 v[136:139], v[214:217], v[222:225], v[136:139]
	global_load_lds_dwordx4 v4, s[48:49]
	v_mfma_f32_16x16x32_bf16 v[84:87], v[218:221], v[222:225], v[84:87]
	ds_read_b128 v[222:225], v26
	v_mfma_f32_16x16x32_bf16 v[150:153], v[214:217], v[226:229], v[150:153]
	ds_read_b128 v[214:217], v23
	v_mfma_f32_16x16x32_bf16 v[154:157], v[218:221], v[226:229], v[154:157]
	ds_read_b128 v[218:221], v22
	ds_read_b128 v[226:229], v27
	s_waitcnt lgkmcnt(6)
	v_mfma_f32_16x16x32_bf16 v[40:43], v[158:161], v[166:169], v[40:43]
	s_waitcnt lgkmcnt(5)
	s_mov_b32 m0, s35
	v_mfma_f32_16x16x32_bf16 v[44:47], v[162:165], v[166:169], v[44:47]
	global_load_lds_dwordx4 v146, s[46:47]
	s_waitcnt lgkmcnt(4)
	v_mfma_f32_16x16x32_bf16 v[56:59], v[158:161], v[178:181], v[56:59]
	v_mfma_f32_16x16x32_bf16 v[60:63], v[162:165], v[178:181], v[60:63]
	s_waitcnt lgkmcnt(3)
	v_mfma_f32_16x16x32_bf16 v[72:75], v[158:161], v[222:225], v[72:75]
	v_mfma_f32_16x16x32_bf16 v[76:79], v[162:165], v[222:225], v[76:79]
	s_waitcnt lgkmcnt(2)
	s_mov_b32 m0, s36
	v_mfma_f32_16x16x32_bf16 v[48:51], v[214:217], v[166:169], v[48:51]
	global_load_lds_dwordx4 v146, s[48:49]
	s_waitcnt lgkmcnt(1)
	v_mfma_f32_16x16x32_bf16 v[174:177], v[218:221], v[166:169], v[174:177]
	ds_read_b128 v[166:169], v28
	v_mfma_f32_16x16x32_bf16 v[64:67], v[214:217], v[178:181], v[64:67]
	v_mfma_f32_16x16x32_bf16 v[170:173], v[218:221], v[178:181], v[170:173]
	ds_read_b128 v[178:181], v29
	v_mfma_f32_16x16x32_bf16 v[80:83], v[214:217], v[222:225], v[80:83]
	v_mfma_f32_16x16x32_bf16 v[32:35], v[218:221], v[222:225], v[32:35]
	ds_read_b128 v[222:225], v30
	s_waitcnt lgkmcnt(3)
	v_mfma_f32_16x16x32_bf16 v[88:91], v[158:161], v[226:229], v[88:91]
	v_mfma_f32_16x16x32_bf16 v[92:95], v[162:165], v[226:229], v[92:95]
	v_mfma_f32_16x16x32_bf16 v[96:99], v[214:217], v[226:229], v[96:99]
	v_mfma_f32_16x16x32_bf16 v[36:39], v[218:221], v[226:229], v[36:39]
	ds_read_b128 v[226:229], v31
	s_waitcnt lgkmcnt(3)
	v_mfma_f32_16x16x32_bf16 v[104:107], v[158:161], v[166:169], v[104:107]
	v_mfma_f32_16x16x32_bf16 v[108:111], v[162:165], v[166:169], v[108:111]
	v_mfma_f32_16x16x32_bf16 v[112:115], v[214:217], v[166:169], v[112:115]
	v_mfma_f32_16x16x32_bf16 v[52:55], v[218:221], v[166:169], v[52:55]
	s_waitcnt lgkmcnt(2)
	v_mfma_f32_16x16x32_bf16 v[116:119], v[158:161], v[178:181], v[116:119]
	v_mfma_f32_16x16x32_bf16 v[120:123], v[162:165], v[178:181], v[120:123]
	v_mfma_f32_16x16x32_bf16 v[124:127], v[214:217], v[178:181], v[124:127]
	v_mfma_f32_16x16x32_bf16 v[68:71], v[218:221], v[178:181], v[68:71]
	s_waitcnt lgkmcnt(1)
	v_mfma_f32_16x16x32_bf16 v[128:131], v[158:161], v[222:225], v[128:131]
	v_mfma_f32_16x16x32_bf16 v[132:135], v[162:165], v[222:225], v[132:135]
	v_mfma_f32_16x16x32_bf16 v[136:139], v[214:217], v[222:225], v[136:139]
	v_mfma_f32_16x16x32_bf16 v[84:87], v[218:221], v[222:225], v[84:87]
	s_waitcnt lgkmcnt(0)
	v_mfma_f32_16x16x32_bf16 v[100:103], v[158:161], v[226:229], v[100:103]
	v_mfma_f32_16x16x32_bf16 v[140:143], v[162:165], v[226:229], v[140:143]
	v_mfma_f32_16x16x32_bf16 v[150:153], v[214:217], v[226:229], v[150:153]
	v_mfma_f32_16x16x32_bf16 v[154:157], v[218:221], v[226:229], v[154:157]
	s_add_u32 s46, s0, 0x1b80
	s_addc_u32 s47, s1, 0
	s_add_u32 s48, s14, 0x1b80
	s_waitcnt vmcnt(0)
	s_barrier
	s_addc_u32 s49, s15, 0
	ds_read_b128 v[158:161], v7 offset:32768
	ds_read_b128 v[162:165], v6
	ds_read_b128 v[166:169], v7 offset:34816
	ds_read_b128 v[178:181], v6 offset:2048
	ds_read_b128 v[214:217], v7 offset:36864
	ds_read_b128 v[218:221], v7 offset:38912
	ds_read_b128 v[222:225], v6 offset:4096
	ds_read_b128 v[226:229], v6 offset:6144
	s_waitcnt lgkmcnt(6)
	v_mfma_f32_16x16x32_bf16 v[40:43], v[158:161], v[162:165], v[40:43]
	s_waitcnt lgkmcnt(5)
	v_mfma_f32_16x16x32_bf16 v[44:47], v[166:169], v[162:165], v[44:47]
	s_waitcnt lgkmcnt(4)
	v_mfma_f32_16x16x32_bf16 v[56:59], v[158:161], v[178:181], v[56:59]
	s_mov_b32 m0, s38
	v_mfma_f32_16x16x32_bf16 v[60:63], v[166:169], v[178:181], v[60:63]
	global_load_lds_dwordx4 v0, s[46:47]
	s_waitcnt lgkmcnt(3)
	v_mfma_f32_16x16x32_bf16 v[48:51], v[214:217], v[162:165], v[48:51]
	v_mfma_f32_16x16x32_bf16 v[64:67], v[214:217], v[178:181], v[64:67]
	s_waitcnt lgkmcnt(2)
	v_mfma_f32_16x16x32_bf16 v[174:177], v[218:221], v[162:165], v[174:177]
	ds_read_b128 v[162:165], v6 offset:8192
	v_mfma_f32_16x16x32_bf16 v[170:173], v[218:221], v[178:181], v[170:173]
	ds_read_b128 v[178:181], v6 offset:10240
	s_waitcnt lgkmcnt(3)
	s_mov_b32 m0, s37
	v_mfma_f32_16x16x32_bf16 v[72:75], v[158:161], v[222:225], v[72:75]
	global_load_lds_dwordx4 v0, s[48:49]
	v_mfma_f32_16x16x32_bf16 v[76:79], v[166:169], v[222:225], v[76:79]
	v_mfma_f32_16x16x32_bf16 v[80:83], v[214:217], v[222:225], v[80:83]
	v_mfma_f32_16x16x32_bf16 v[32:35], v[218:221], v[222:225], v[32:35]
	ds_read_b128 v[222:225], v6 offset:12288
	s_waitcnt lgkmcnt(3)
	v_mfma_f32_16x16x32_bf16 v[88:91], v[158:161], v[226:229], v[88:91]
	s_mov_b32 m0, s39
	v_mfma_f32_16x16x32_bf16 v[92:95], v[166:169], v[226:229], v[92:95]
	global_load_lds_dwordx4 v2, s[46:47]
	v_mfma_f32_16x16x32_bf16 v[96:99], v[214:217], v[226:229], v[96:99]
	v_mfma_f32_16x16x32_bf16 v[36:39], v[218:221], v[226:229], v[36:39]
	ds_read_b128 v[226:229], v6 offset:14336
	s_waitcnt lgkmcnt(3)
	v_mfma_f32_16x16x32_bf16 v[104:107], v[158:161], v[162:165], v[104:107]
	s_waitcnt lgkmcnt(2)
	v_mfma_f32_16x16x32_bf16 v[116:119], v[158:161], v[178:181], v[116:119]
	s_waitcnt lgkmcnt(1)
	s_mov_b32 m0, s40
	v_mfma_f32_16x16x32_bf16 v[128:131], v[158:161], v[222:225], v[128:131]
	global_load_lds_dwordx4 v2, s[48:49]
	s_waitcnt lgkmcnt(0)
	v_mfma_f32_16x16x32_bf16 v[100:103], v[158:161], v[226:229], v[100:103]
	ds_read_b128 v[158:161], v7 offset:33792
	v_mfma_f32_16x16x32_bf16 v[108:111], v[166:169], v[162:165], v[108:111]
	v_mfma_f32_16x16x32_bf16 v[120:123], v[166:169], v[178:181], v[120:123]
	v_mfma_f32_16x16x32_bf16 v[132:135], v[166:169], v[222:225], v[132:135]
	s_mov_b32 m0, s41
	v_mfma_f32_16x16x32_bf16 v[140:143], v[166:169], v[226:229], v[140:143]
	global_load_lds_dwordx4 v4, s[46:47]
	ds_read_b128 v[166:169], v6 offset:1024
	v_mfma_f32_16x16x32_bf16 v[112:115], v[214:217], v[162:165], v[112:115]
	v_mfma_f32_16x16x32_bf16 v[52:55], v[218:221], v[162:165], v[52:55]
	ds_read_b128 v[162:165], v7 offset:35840
	v_mfma_f32_16x16x32_bf16 v[124:127], v[214:217], v[178:181], v[124:127]
	v_mfma_f32_16x16x32_bf16 v[68:71], v[218:221], v[178:181], v[68:71]
	ds_read_b128 v[178:181], v6 offset:3072
	s_mov_b32 m0, s42
	v_mfma_f32_16x16x32_bf16 v[136:139], v[214:217], v[222:225], v[136:139]
	global_load_lds_dwordx4 v4, s[48:49]
	v_mfma_f32_16x16x32_bf16 v[84:87], v[218:221], v[222:225], v[84:87]
	ds_read_b128 v[222:225], v6 offset:5120
	v_mfma_f32_16x16x32_bf16 v[150:153], v[214:217], v[226:229], v[150:153]
	ds_read_b128 v[214:217], v7 offset:37888
	v_mfma_f32_16x16x32_bf16 v[154:157], v[218:221], v[226:229], v[154:157]
	ds_read_b128 v[218:221], v7 offset:39936
	ds_read_b128 v[226:229], v6 offset:7168
	s_waitcnt lgkmcnt(6)
	v_mfma_f32_16x16x32_bf16 v[40:43], v[158:161], v[166:169], v[40:43]
	s_waitcnt lgkmcnt(5)
	s_mov_b32 m0, s43
	v_mfma_f32_16x16x32_bf16 v[44:47], v[162:165], v[166:169], v[44:47]
	global_load_lds_dwordx4 v146, s[46:47]
	s_waitcnt lgkmcnt(4)
	v_mfma_f32_16x16x32_bf16 v[56:59], v[158:161], v[178:181], v[56:59]
	v_mfma_f32_16x16x32_bf16 v[60:63], v[162:165], v[178:181], v[60:63]
	s_waitcnt lgkmcnt(3)
	v_mfma_f32_16x16x32_bf16 v[72:75], v[158:161], v[222:225], v[72:75]
	v_mfma_f32_16x16x32_bf16 v[76:79], v[162:165], v[222:225], v[76:79]
	s_waitcnt lgkmcnt(2)
	s_mov_b32 m0, s44
	v_mfma_f32_16x16x32_bf16 v[48:51], v[214:217], v[166:169], v[48:51]
	global_load_lds_dwordx4 v146, s[48:49]
	s_waitcnt lgkmcnt(1)
	v_mfma_f32_16x16x32_bf16 v[174:177], v[218:221], v[166:169], v[174:177]
	ds_read_b128 v[166:169], v6 offset:9216
	v_mfma_f32_16x16x32_bf16 v[64:67], v[214:217], v[178:181], v[64:67]
	v_mfma_f32_16x16x32_bf16 v[170:173], v[218:221], v[178:181], v[170:173]
	ds_read_b128 v[178:181], v6 offset:11264
	v_mfma_f32_16x16x32_bf16 v[80:83], v[214:217], v[222:225], v[80:83]
	v_mfma_f32_16x16x32_bf16 v[32:35], v[218:221], v[222:225], v[32:35]
	ds_read_b128 v[222:225], v6 offset:13312
	s_waitcnt lgkmcnt(3)
	v_mfma_f32_16x16x32_bf16 v[88:91], v[158:161], v[226:229], v[88:91]
	v_mfma_f32_16x16x32_bf16 v[92:95], v[162:165], v[226:229], v[92:95]
	v_mfma_f32_16x16x32_bf16 v[96:99], v[214:217], v[226:229], v[96:99]
	v_mfma_f32_16x16x32_bf16 v[36:39], v[218:221], v[226:229], v[36:39]
	ds_read_b128 v[226:229], v6 offset:15360
	s_waitcnt lgkmcnt(3)
	v_mfma_f32_16x16x32_bf16 v[104:107], v[158:161], v[166:169], v[104:107]
	v_mfma_f32_16x16x32_bf16 v[108:111], v[162:165], v[166:169], v[108:111]
	v_mfma_f32_16x16x32_bf16 v[112:115], v[214:217], v[166:169], v[112:115]
	v_mfma_f32_16x16x32_bf16 v[52:55], v[218:221], v[166:169], v[52:55]
	s_waitcnt lgkmcnt(2)
	v_mfma_f32_16x16x32_bf16 v[116:119], v[158:161], v[178:181], v[116:119]
	v_mfma_f32_16x16x32_bf16 v[120:123], v[162:165], v[178:181], v[120:123]
	v_mfma_f32_16x16x32_bf16 v[124:127], v[214:217], v[178:181], v[124:127]
	v_mfma_f32_16x16x32_bf16 v[68:71], v[218:221], v[178:181], v[68:71]
	s_waitcnt lgkmcnt(1)
	v_mfma_f32_16x16x32_bf16 v[128:131], v[158:161], v[222:225], v[128:131]
	v_mfma_f32_16x16x32_bf16 v[132:135], v[162:165], v[222:225], v[132:135]
	v_mfma_f32_16x16x32_bf16 v[136:139], v[214:217], v[222:225], v[136:139]
	v_mfma_f32_16x16x32_bf16 v[84:87], v[218:221], v[222:225], v[84:87]
	s_waitcnt lgkmcnt(0)
	v_mfma_f32_16x16x32_bf16 v[100:103], v[158:161], v[226:229], v[100:103]
	v_mfma_f32_16x16x32_bf16 v[140:143], v[162:165], v[226:229], v[140:143]
	v_mfma_f32_16x16x32_bf16 v[150:153], v[214:217], v[226:229], v[150:153]
	v_mfma_f32_16x16x32_bf16 v[154:157], v[218:221], v[226:229], v[154:157]
	s_add_u32 s46, s0, 0x1c00
	s_addc_u32 s47, s1, 0
	s_add_u32 s48, s14, 0x1c00
	s_waitcnt vmcnt(0)
	s_barrier
	s_addc_u32 s49, s15, 0
	ds_read_b128 v[158:161], v8
	ds_read_b128 v[162:165], v12
	ds_read_b128 v[166:169], v9
	ds_read_b128 v[178:181], v13
	ds_read_b128 v[214:217], v11
	ds_read_b128 v[218:221], v10
	ds_read_b128 v[222:225], v14
	ds_read_b128 v[226:229], v15
	s_waitcnt lgkmcnt(6)
	v_mfma_f32_16x16x32_bf16 v[40:43], v[158:161], v[162:165], v[40:43]
	s_waitcnt lgkmcnt(5)
	v_mfma_f32_16x16x32_bf16 v[44:47], v[166:169], v[162:165], v[44:47]
	s_waitcnt lgkmcnt(4)
	v_mfma_f32_16x16x32_bf16 v[56:59], v[158:161], v[178:181], v[56:59]
	s_mov_b32 m0, s27
	v_mfma_f32_16x16x32_bf16 v[60:63], v[166:169], v[178:181], v[60:63]
	global_load_lds_dwordx4 v0, s[46:47]
	s_waitcnt lgkmcnt(3)
	v_mfma_f32_16x16x32_bf16 v[48:51], v[214:217], v[162:165], v[48:51]
	v_mfma_f32_16x16x32_bf16 v[64:67], v[214:217], v[178:181], v[64:67]
	s_waitcnt lgkmcnt(2)
	v_mfma_f32_16x16x32_bf16 v[174:177], v[218:221], v[162:165], v[174:177]
	ds_read_b128 v[162:165], v16
	v_mfma_f32_16x16x32_bf16 v[170:173], v[218:221], v[178:181], v[170:173]
	ds_read_b128 v[178:181], v17
	s_waitcnt lgkmcnt(3)
	s_mov_b32 m0, s28
	v_mfma_f32_16x16x32_bf16 v[72:75], v[158:161], v[222:225], v[72:75]
	global_load_lds_dwordx4 v0, s[48:49]
	v_mfma_f32_16x16x32_bf16 v[76:79], v[166:169], v[222:225], v[76:79]
	v_mfma_f32_16x16x32_bf16 v[80:83], v[214:217], v[222:225], v[80:83]
	v_mfma_f32_16x16x32_bf16 v[32:35], v[218:221], v[222:225], v[32:35]
	ds_read_b128 v[222:225], v18
	s_waitcnt lgkmcnt(3)
	v_mfma_f32_16x16x32_bf16 v[88:91], v[158:161], v[226:229], v[88:91]
	s_mov_b32 m0, s29
	v_mfma_f32_16x16x32_bf16 v[92:95], v[166:169], v[226:229], v[92:95]
	global_load_lds_dwordx4 v2, s[46:47]
	v_mfma_f32_16x16x32_bf16 v[96:99], v[214:217], v[226:229], v[96:99]
	v_mfma_f32_16x16x32_bf16 v[36:39], v[218:221], v[226:229], v[36:39]
	ds_read_b128 v[226:229], v19
	s_waitcnt lgkmcnt(3)
	v_mfma_f32_16x16x32_bf16 v[104:107], v[158:161], v[162:165], v[104:107]
	s_waitcnt lgkmcnt(2)
	v_mfma_f32_16x16x32_bf16 v[116:119], v[158:161], v[178:181], v[116:119]
	s_waitcnt lgkmcnt(1)
	s_mov_b32 m0, s30
	v_mfma_f32_16x16x32_bf16 v[128:131], v[158:161], v[222:225], v[128:131]
	global_load_lds_dwordx4 v2, s[48:49]
	s_waitcnt lgkmcnt(0)
	v_mfma_f32_16x16x32_bf16 v[100:103], v[158:161], v[226:229], v[100:103]
	ds_read_b128 v[158:161], v20
	v_mfma_f32_16x16x32_bf16 v[108:111], v[166:169], v[162:165], v[108:111]
	v_mfma_f32_16x16x32_bf16 v[120:123], v[166:169], v[178:181], v[120:123]
	v_mfma_f32_16x16x32_bf16 v[132:135], v[166:169], v[222:225], v[132:135]
	s_mov_b32 m0, s31
	v_mfma_f32_16x16x32_bf16 v[140:143], v[166:169], v[226:229], v[140:143]
	global_load_lds_dwordx4 v4, s[46:47]
	ds_read_b128 v[166:169], v24
	v_mfma_f32_16x16x32_bf16 v[112:115], v[214:217], v[162:165], v[112:115]
	v_mfma_f32_16x16x32_bf16 v[52:55], v[218:221], v[162:165], v[52:55]
	ds_read_b128 v[162:165], v21
	v_mfma_f32_16x16x32_bf16 v[124:127], v[214:217], v[178:181], v[124:127]
	v_mfma_f32_16x16x32_bf16 v[68:71], v[218:221], v[178:181], v[68:71]
	ds_read_b128 v[178:181], v25
	s_mov_b32 m0, s34
	v_mfma_f32_16x16x32_bf16 v[136:139], v[214:217], v[222:225], v[136:139]
	global_load_lds_dwordx4 v4, s[48:49]
	v_mfma_f32_16x16x32_bf16 v[84:87], v[218:221], v[222:225], v[84:87]
	ds_read_b128 v[222:225], v26
	v_mfma_f32_16x16x32_bf16 v[150:153], v[214:217], v[226:229], v[150:153]
	ds_read_b128 v[214:217], v23
	v_mfma_f32_16x16x32_bf16 v[154:157], v[218:221], v[226:229], v[154:157]
	ds_read_b128 v[218:221], v22
	ds_read_b128 v[226:229], v27
	s_waitcnt lgkmcnt(6)
	v_mfma_f32_16x16x32_bf16 v[40:43], v[158:161], v[166:169], v[40:43]
	s_waitcnt lgkmcnt(5)
	s_mov_b32 m0, s35
	v_mfma_f32_16x16x32_bf16 v[44:47], v[162:165], v[166:169], v[44:47]
	global_load_lds_dwordx4 v146, s[46:47]
	s_waitcnt lgkmcnt(4)
	v_mfma_f32_16x16x32_bf16 v[56:59], v[158:161], v[178:181], v[56:59]
	v_mfma_f32_16x16x32_bf16 v[60:63], v[162:165], v[178:181], v[60:63]
	s_waitcnt lgkmcnt(3)
	v_mfma_f32_16x16x32_bf16 v[72:75], v[158:161], v[222:225], v[72:75]
	v_mfma_f32_16x16x32_bf16 v[76:79], v[162:165], v[222:225], v[76:79]
	s_waitcnt lgkmcnt(2)
	s_mov_b32 m0, s36
	v_mfma_f32_16x16x32_bf16 v[48:51], v[214:217], v[166:169], v[48:51]
	global_load_lds_dwordx4 v146, s[48:49]
	s_waitcnt lgkmcnt(1)
	v_mfma_f32_16x16x32_bf16 v[174:177], v[218:221], v[166:169], v[174:177]
	ds_read_b128 v[166:169], v28
	v_mfma_f32_16x16x32_bf16 v[64:67], v[214:217], v[178:181], v[64:67]
	v_mfma_f32_16x16x32_bf16 v[170:173], v[218:221], v[178:181], v[170:173]
	ds_read_b128 v[178:181], v29
	v_mfma_f32_16x16x32_bf16 v[80:83], v[214:217], v[222:225], v[80:83]
	v_mfma_f32_16x16x32_bf16 v[32:35], v[218:221], v[222:225], v[32:35]
	ds_read_b128 v[222:225], v30
	s_waitcnt lgkmcnt(3)
	v_mfma_f32_16x16x32_bf16 v[88:91], v[158:161], v[226:229], v[88:91]
	v_mfma_f32_16x16x32_bf16 v[92:95], v[162:165], v[226:229], v[92:95]
	v_mfma_f32_16x16x32_bf16 v[96:99], v[214:217], v[226:229], v[96:99]
	v_mfma_f32_16x16x32_bf16 v[36:39], v[218:221], v[226:229], v[36:39]
	ds_read_b128 v[226:229], v31
	s_waitcnt lgkmcnt(3)
	v_mfma_f32_16x16x32_bf16 v[104:107], v[158:161], v[166:169], v[104:107]
	v_mfma_f32_16x16x32_bf16 v[108:111], v[162:165], v[166:169], v[108:111]
	v_mfma_f32_16x16x32_bf16 v[112:115], v[214:217], v[166:169], v[112:115]
	v_mfma_f32_16x16x32_bf16 v[52:55], v[218:221], v[166:169], v[52:55]
	s_waitcnt lgkmcnt(2)
	v_mfma_f32_16x16x32_bf16 v[116:119], v[158:161], v[178:181], v[116:119]
	v_mfma_f32_16x16x32_bf16 v[120:123], v[162:165], v[178:181], v[120:123]
	v_mfma_f32_16x16x32_bf16 v[124:127], v[214:217], v[178:181], v[124:127]
	v_mfma_f32_16x16x32_bf16 v[68:71], v[218:221], v[178:181], v[68:71]
	s_waitcnt lgkmcnt(1)
	v_mfma_f32_16x16x32_bf16 v[128:131], v[158:161], v[222:225], v[128:131]
	v_mfma_f32_16x16x32_bf16 v[132:135], v[162:165], v[222:225], v[132:135]
	v_mfma_f32_16x16x32_bf16 v[136:139], v[214:217], v[222:225], v[136:139]
	v_mfma_f32_16x16x32_bf16 v[84:87], v[218:221], v[222:225], v[84:87]
	s_waitcnt lgkmcnt(0)
	v_mfma_f32_16x16x32_bf16 v[100:103], v[158:161], v[226:229], v[100:103]
	v_mfma_f32_16x16x32_bf16 v[140:143], v[162:165], v[226:229], v[140:143]
	v_mfma_f32_16x16x32_bf16 v[150:153], v[214:217], v[226:229], v[150:153]
	v_mfma_f32_16x16x32_bf16 v[154:157], v[218:221], v[226:229], v[154:157]
	s_add_u32 s46, s0, 0x1c80
	s_addc_u32 s47, s1, 0
	s_add_u32 s48, s14, 0x1c80
	s_waitcnt vmcnt(0)
	s_barrier
	s_addc_u32 s49, s15, 0
	ds_read_b128 v[158:161], v7 offset:32768
	ds_read_b128 v[162:165], v6
	ds_read_b128 v[166:169], v7 offset:34816
	ds_read_b128 v[178:181], v6 offset:2048
	ds_read_b128 v[214:217], v7 offset:36864
	ds_read_b128 v[218:221], v7 offset:38912
	ds_read_b128 v[222:225], v6 offset:4096
	ds_read_b128 v[226:229], v6 offset:6144
	s_waitcnt lgkmcnt(6)
	v_mfma_f32_16x16x32_bf16 v[40:43], v[158:161], v[162:165], v[40:43]
	s_waitcnt lgkmcnt(5)
	v_mfma_f32_16x16x32_bf16 v[44:47], v[166:169], v[162:165], v[44:47]
	s_waitcnt lgkmcnt(4)
	v_mfma_f32_16x16x32_bf16 v[56:59], v[158:161], v[178:181], v[56:59]
	s_mov_b32 m0, s38
	v_mfma_f32_16x16x32_bf16 v[60:63], v[166:169], v[178:181], v[60:63]
	global_load_lds_dwordx4 v0, s[46:47]
	s_waitcnt lgkmcnt(3)
	v_mfma_f32_16x16x32_bf16 v[48:51], v[214:217], v[162:165], v[48:51]
	v_mfma_f32_16x16x32_bf16 v[64:67], v[214:217], v[178:181], v[64:67]
	s_waitcnt lgkmcnt(2)
	v_mfma_f32_16x16x32_bf16 v[174:177], v[218:221], v[162:165], v[174:177]
	ds_read_b128 v[162:165], v6 offset:8192
	v_mfma_f32_16x16x32_bf16 v[170:173], v[218:221], v[178:181], v[170:173]
	ds_read_b128 v[178:181], v6 offset:10240
	s_waitcnt lgkmcnt(3)
	s_mov_b32 m0, s37
	v_mfma_f32_16x16x32_bf16 v[72:75], v[158:161], v[222:225], v[72:75]
	global_load_lds_dwordx4 v0, s[48:49]
	v_mfma_f32_16x16x32_bf16 v[76:79], v[166:169], v[222:225], v[76:79]
	v_mfma_f32_16x16x32_bf16 v[80:83], v[214:217], v[222:225], v[80:83]
	v_mfma_f32_16x16x32_bf16 v[32:35], v[218:221], v[222:225], v[32:35]
	ds_read_b128 v[222:225], v6 offset:12288
	s_waitcnt lgkmcnt(3)
	v_mfma_f32_16x16x32_bf16 v[88:91], v[158:161], v[226:229], v[88:91]
	s_mov_b32 m0, s39
	v_mfma_f32_16x16x32_bf16 v[92:95], v[166:169], v[226:229], v[92:95]
	global_load_lds_dwordx4 v2, s[46:47]
	v_mfma_f32_16x16x32_bf16 v[96:99], v[214:217], v[226:229], v[96:99]
	v_mfma_f32_16x16x32_bf16 v[36:39], v[218:221], v[226:229], v[36:39]
	ds_read_b128 v[226:229], v6 offset:14336
	s_waitcnt lgkmcnt(3)
	v_mfma_f32_16x16x32_bf16 v[104:107], v[158:161], v[162:165], v[104:107]
	s_waitcnt lgkmcnt(2)
	v_mfma_f32_16x16x32_bf16 v[116:119], v[158:161], v[178:181], v[116:119]
	s_waitcnt lgkmcnt(1)
	s_mov_b32 m0, s40
	v_mfma_f32_16x16x32_bf16 v[128:131], v[158:161], v[222:225], v[128:131]
	global_load_lds_dwordx4 v2, s[48:49]
	s_waitcnt lgkmcnt(0)
	v_mfma_f32_16x16x32_bf16 v[100:103], v[158:161], v[226:229], v[100:103]
	ds_read_b128 v[158:161], v7 offset:33792
	v_mfma_f32_16x16x32_bf16 v[108:111], v[166:169], v[162:165], v[108:111]
	v_mfma_f32_16x16x32_bf16 v[120:123], v[166:169], v[178:181], v[120:123]
	v_mfma_f32_16x16x32_bf16 v[132:135], v[166:169], v[222:225], v[132:135]
	s_mov_b32 m0, s41
	v_mfma_f32_16x16x32_bf16 v[140:143], v[166:169], v[226:229], v[140:143]
	global_load_lds_dwordx4 v4, s[46:47]
	ds_read_b128 v[166:169], v6 offset:1024
	v_mfma_f32_16x16x32_bf16 v[112:115], v[214:217], v[162:165], v[112:115]
	v_mfma_f32_16x16x32_bf16 v[52:55], v[218:221], v[162:165], v[52:55]
	ds_read_b128 v[162:165], v7 offset:35840
	v_mfma_f32_16x16x32_bf16 v[124:127], v[214:217], v[178:181], v[124:127]
	v_mfma_f32_16x16x32_bf16 v[68:71], v[218:221], v[178:181], v[68:71]
	ds_read_b128 v[178:181], v6 offset:3072
	s_mov_b32 m0, s42
	v_mfma_f32_16x16x32_bf16 v[136:139], v[214:217], v[222:225], v[136:139]
	global_load_lds_dwordx4 v4, s[48:49]
	v_mfma_f32_16x16x32_bf16 v[84:87], v[218:221], v[222:225], v[84:87]
	ds_read_b128 v[222:225], v6 offset:5120
	v_mfma_f32_16x16x32_bf16 v[150:153], v[214:217], v[226:229], v[150:153]
	ds_read_b128 v[214:217], v7 offset:37888
	v_mfma_f32_16x16x32_bf16 v[154:157], v[218:221], v[226:229], v[154:157]
	ds_read_b128 v[218:221], v7 offset:39936
	ds_read_b128 v[226:229], v6 offset:7168
	s_waitcnt lgkmcnt(6)
	v_mfma_f32_16x16x32_bf16 v[40:43], v[158:161], v[166:169], v[40:43]
	s_waitcnt lgkmcnt(5)
	s_mov_b32 m0, s43
	v_mfma_f32_16x16x32_bf16 v[44:47], v[162:165], v[166:169], v[44:47]
	global_load_lds_dwordx4 v146, s[46:47]
	s_waitcnt lgkmcnt(4)
	v_mfma_f32_16x16x32_bf16 v[56:59], v[158:161], v[178:181], v[56:59]
	v_mfma_f32_16x16x32_bf16 v[60:63], v[162:165], v[178:181], v[60:63]
	s_waitcnt lgkmcnt(3)
	v_mfma_f32_16x16x32_bf16 v[72:75], v[158:161], v[222:225], v[72:75]
	v_mfma_f32_16x16x32_bf16 v[76:79], v[162:165], v[222:225], v[76:79]
	s_waitcnt lgkmcnt(2)
	s_mov_b32 m0, s44
	v_mfma_f32_16x16x32_bf16 v[48:51], v[214:217], v[166:169], v[48:51]
	global_load_lds_dwordx4 v146, s[48:49]
	s_waitcnt lgkmcnt(1)
	v_mfma_f32_16x16x32_bf16 v[174:177], v[218:221], v[166:169], v[174:177]
	ds_read_b128 v[166:169], v6 offset:9216
	v_mfma_f32_16x16x32_bf16 v[64:67], v[214:217], v[178:181], v[64:67]
	v_mfma_f32_16x16x32_bf16 v[170:173], v[218:221], v[178:181], v[170:173]
	ds_read_b128 v[178:181], v6 offset:11264
	v_mfma_f32_16x16x32_bf16 v[80:83], v[214:217], v[222:225], v[80:83]
	v_mfma_f32_16x16x32_bf16 v[32:35], v[218:221], v[222:225], v[32:35]
	ds_read_b128 v[222:225], v6 offset:13312
	s_waitcnt lgkmcnt(3)
	v_mfma_f32_16x16x32_bf16 v[88:91], v[158:161], v[226:229], v[88:91]
	v_mfma_f32_16x16x32_bf16 v[92:95], v[162:165], v[226:229], v[92:95]
	v_mfma_f32_16x16x32_bf16 v[96:99], v[214:217], v[226:229], v[96:99]
	v_mfma_f32_16x16x32_bf16 v[36:39], v[218:221], v[226:229], v[36:39]
	ds_read_b128 v[226:229], v6 offset:15360
	s_waitcnt lgkmcnt(3)
	v_mfma_f32_16x16x32_bf16 v[104:107], v[158:161], v[166:169], v[104:107]
	v_mfma_f32_16x16x32_bf16 v[108:111], v[162:165], v[166:169], v[108:111]
	v_mfma_f32_16x16x32_bf16 v[112:115], v[214:217], v[166:169], v[112:115]
	v_mfma_f32_16x16x32_bf16 v[52:55], v[218:221], v[166:169], v[52:55]
	s_waitcnt lgkmcnt(2)
	v_mfma_f32_16x16x32_bf16 v[116:119], v[158:161], v[178:181], v[116:119]
	v_mfma_f32_16x16x32_bf16 v[120:123], v[162:165], v[178:181], v[120:123]
	v_mfma_f32_16x16x32_bf16 v[124:127], v[214:217], v[178:181], v[124:127]
	v_mfma_f32_16x16x32_bf16 v[68:71], v[218:221], v[178:181], v[68:71]
	s_waitcnt lgkmcnt(1)
	v_mfma_f32_16x16x32_bf16 v[128:131], v[158:161], v[222:225], v[128:131]
	v_mfma_f32_16x16x32_bf16 v[132:135], v[162:165], v[222:225], v[132:135]
	v_mfma_f32_16x16x32_bf16 v[136:139], v[214:217], v[222:225], v[136:139]
	v_mfma_f32_16x16x32_bf16 v[84:87], v[218:221], v[222:225], v[84:87]
	s_waitcnt lgkmcnt(0)
	v_mfma_f32_16x16x32_bf16 v[100:103], v[158:161], v[226:229], v[100:103]
	v_mfma_f32_16x16x32_bf16 v[140:143], v[162:165], v[226:229], v[140:143]
	v_mfma_f32_16x16x32_bf16 v[150:153], v[214:217], v[226:229], v[150:153]
	v_mfma_f32_16x16x32_bf16 v[154:157], v[218:221], v[226:229], v[154:157]
	s_add_u32 s46, s0, 0x1d00
	s_addc_u32 s47, s1, 0
	s_add_u32 s48, s14, 0x1d00
	s_waitcnt vmcnt(0)
	s_barrier
	s_addc_u32 s49, s15, 0
	ds_read_b128 v[158:161], v8
	ds_read_b128 v[162:165], v12
	ds_read_b128 v[166:169], v9
	ds_read_b128 v[178:181], v13
	ds_read_b128 v[214:217], v11
	ds_read_b128 v[218:221], v10
	ds_read_b128 v[222:225], v14
	ds_read_b128 v[226:229], v15
	s_waitcnt lgkmcnt(6)
	v_mfma_f32_16x16x32_bf16 v[40:43], v[158:161], v[162:165], v[40:43]
	s_waitcnt lgkmcnt(5)
	v_mfma_f32_16x16x32_bf16 v[44:47], v[166:169], v[162:165], v[44:47]
	s_waitcnt lgkmcnt(4)
	v_mfma_f32_16x16x32_bf16 v[56:59], v[158:161], v[178:181], v[56:59]
	s_mov_b32 m0, s27
	v_mfma_f32_16x16x32_bf16 v[60:63], v[166:169], v[178:181], v[60:63]
	global_load_lds_dwordx4 v0, s[46:47]
	s_waitcnt lgkmcnt(3)
	v_mfma_f32_16x16x32_bf16 v[48:51], v[214:217], v[162:165], v[48:51]
	v_mfma_f32_16x16x32_bf16 v[64:67], v[214:217], v[178:181], v[64:67]
	s_waitcnt lgkmcnt(2)
	v_mfma_f32_16x16x32_bf16 v[174:177], v[218:221], v[162:165], v[174:177]
	ds_read_b128 v[162:165], v16
	v_mfma_f32_16x16x32_bf16 v[170:173], v[218:221], v[178:181], v[170:173]
	ds_read_b128 v[178:181], v17
	s_waitcnt lgkmcnt(3)
	s_mov_b32 m0, s28
	v_mfma_f32_16x16x32_bf16 v[72:75], v[158:161], v[222:225], v[72:75]
	global_load_lds_dwordx4 v0, s[48:49]
	v_mfma_f32_16x16x32_bf16 v[76:79], v[166:169], v[222:225], v[76:79]
	v_mfma_f32_16x16x32_bf16 v[80:83], v[214:217], v[222:225], v[80:83]
	v_mfma_f32_16x16x32_bf16 v[32:35], v[218:221], v[222:225], v[32:35]
	ds_read_b128 v[222:225], v18
	s_waitcnt lgkmcnt(3)
	v_mfma_f32_16x16x32_bf16 v[88:91], v[158:161], v[226:229], v[88:91]
	s_mov_b32 m0, s29
	v_mfma_f32_16x16x32_bf16 v[92:95], v[166:169], v[226:229], v[92:95]
	global_load_lds_dwordx4 v2, s[46:47]
	v_mfma_f32_16x16x32_bf16 v[96:99], v[214:217], v[226:229], v[96:99]
	v_mfma_f32_16x16x32_bf16 v[36:39], v[218:221], v[226:229], v[36:39]
	ds_read_b128 v[226:229], v19
	s_waitcnt lgkmcnt(3)
	v_mfma_f32_16x16x32_bf16 v[104:107], v[158:161], v[162:165], v[104:107]
	s_waitcnt lgkmcnt(2)
	v_mfma_f32_16x16x32_bf16 v[116:119], v[158:161], v[178:181], v[116:119]
	s_waitcnt lgkmcnt(1)
	s_mov_b32 m0, s30
	v_mfma_f32_16x16x32_bf16 v[128:131], v[158:161], v[222:225], v[128:131]
	global_load_lds_dwordx4 v2, s[48:49]
	s_waitcnt lgkmcnt(0)
	v_mfma_f32_16x16x32_bf16 v[100:103], v[158:161], v[226:229], v[100:103]
	ds_read_b128 v[158:161], v20
	v_mfma_f32_16x16x32_bf16 v[108:111], v[166:169], v[162:165], v[108:111]
	v_mfma_f32_16x16x32_bf16 v[120:123], v[166:169], v[178:181], v[120:123]
	v_mfma_f32_16x16x32_bf16 v[132:135], v[166:169], v[222:225], v[132:135]
	s_mov_b32 m0, s31
	v_mfma_f32_16x16x32_bf16 v[140:143], v[166:169], v[226:229], v[140:143]
	global_load_lds_dwordx4 v4, s[46:47]
	ds_read_b128 v[166:169], v24
	v_mfma_f32_16x16x32_bf16 v[112:115], v[214:217], v[162:165], v[112:115]
	v_mfma_f32_16x16x32_bf16 v[52:55], v[218:221], v[162:165], v[52:55]
	ds_read_b128 v[162:165], v21
	v_mfma_f32_16x16x32_bf16 v[124:127], v[214:217], v[178:181], v[124:127]
	v_mfma_f32_16x16x32_bf16 v[68:71], v[218:221], v[178:181], v[68:71]
	ds_read_b128 v[178:181], v25
	s_mov_b32 m0, s34
	v_mfma_f32_16x16x32_bf16 v[136:139], v[214:217], v[222:225], v[136:139]
	global_load_lds_dwordx4 v4, s[48:49]
	v_mfma_f32_16x16x32_bf16 v[84:87], v[218:221], v[222:225], v[84:87]
	ds_read_b128 v[222:225], v26
	v_mfma_f32_16x16x32_bf16 v[150:153], v[214:217], v[226:229], v[150:153]
	ds_read_b128 v[214:217], v23
	v_mfma_f32_16x16x32_bf16 v[154:157], v[218:221], v[226:229], v[154:157]
	ds_read_b128 v[218:221], v22
	ds_read_b128 v[226:229], v27
	s_waitcnt lgkmcnt(6)
	v_mfma_f32_16x16x32_bf16 v[40:43], v[158:161], v[166:169], v[40:43]
	s_waitcnt lgkmcnt(5)
	s_mov_b32 m0, s35
	v_mfma_f32_16x16x32_bf16 v[44:47], v[162:165], v[166:169], v[44:47]
	global_load_lds_dwordx4 v146, s[46:47]
	s_waitcnt lgkmcnt(4)
	v_mfma_f32_16x16x32_bf16 v[56:59], v[158:161], v[178:181], v[56:59]
	v_mfma_f32_16x16x32_bf16 v[60:63], v[162:165], v[178:181], v[60:63]
	s_waitcnt lgkmcnt(3)
	v_mfma_f32_16x16x32_bf16 v[72:75], v[158:161], v[222:225], v[72:75]
	v_mfma_f32_16x16x32_bf16 v[76:79], v[162:165], v[222:225], v[76:79]
	s_waitcnt lgkmcnt(2)
	s_mov_b32 m0, s36
	v_mfma_f32_16x16x32_bf16 v[48:51], v[214:217], v[166:169], v[48:51]
	global_load_lds_dwordx4 v146, s[48:49]
	s_waitcnt lgkmcnt(1)
	v_mfma_f32_16x16x32_bf16 v[174:177], v[218:221], v[166:169], v[174:177]
	ds_read_b128 v[166:169], v28
	v_mfma_f32_16x16x32_bf16 v[64:67], v[214:217], v[178:181], v[64:67]
	v_mfma_f32_16x16x32_bf16 v[170:173], v[218:221], v[178:181], v[170:173]
	ds_read_b128 v[178:181], v29
	v_mfma_f32_16x16x32_bf16 v[80:83], v[214:217], v[222:225], v[80:83]
	v_mfma_f32_16x16x32_bf16 v[32:35], v[218:221], v[222:225], v[32:35]
	ds_read_b128 v[222:225], v30
	s_waitcnt lgkmcnt(3)
	v_mfma_f32_16x16x32_bf16 v[88:91], v[158:161], v[226:229], v[88:91]
	v_mfma_f32_16x16x32_bf16 v[92:95], v[162:165], v[226:229], v[92:95]
	v_mfma_f32_16x16x32_bf16 v[96:99], v[214:217], v[226:229], v[96:99]
	v_mfma_f32_16x16x32_bf16 v[36:39], v[218:221], v[226:229], v[36:39]
	ds_read_b128 v[226:229], v31
	s_waitcnt lgkmcnt(3)
	v_mfma_f32_16x16x32_bf16 v[104:107], v[158:161], v[166:169], v[104:107]
	v_mfma_f32_16x16x32_bf16 v[108:111], v[162:165], v[166:169], v[108:111]
	v_mfma_f32_16x16x32_bf16 v[112:115], v[214:217], v[166:169], v[112:115]
	v_mfma_f32_16x16x32_bf16 v[52:55], v[218:221], v[166:169], v[52:55]
	s_waitcnt lgkmcnt(2)
	v_mfma_f32_16x16x32_bf16 v[116:119], v[158:161], v[178:181], v[116:119]
	v_mfma_f32_16x16x32_bf16 v[120:123], v[162:165], v[178:181], v[120:123]
	v_mfma_f32_16x16x32_bf16 v[124:127], v[214:217], v[178:181], v[124:127]
	v_mfma_f32_16x16x32_bf16 v[68:71], v[218:221], v[178:181], v[68:71]
	s_waitcnt lgkmcnt(1)
	v_mfma_f32_16x16x32_bf16 v[128:131], v[158:161], v[222:225], v[128:131]
	v_mfma_f32_16x16x32_bf16 v[132:135], v[162:165], v[222:225], v[132:135]
	v_mfma_f32_16x16x32_bf16 v[136:139], v[214:217], v[222:225], v[136:139]
	v_mfma_f32_16x16x32_bf16 v[84:87], v[218:221], v[222:225], v[84:87]
	s_waitcnt lgkmcnt(0)
	v_mfma_f32_16x16x32_bf16 v[100:103], v[158:161], v[226:229], v[100:103]
	v_mfma_f32_16x16x32_bf16 v[140:143], v[162:165], v[226:229], v[140:143]
	v_mfma_f32_16x16x32_bf16 v[150:153], v[214:217], v[226:229], v[150:153]
	v_mfma_f32_16x16x32_bf16 v[154:157], v[218:221], v[226:229], v[154:157]
	s_add_u32 s46, s0, 0x1d80
	s_addc_u32 s47, s1, 0
	s_add_u32 s48, s14, 0x1d80
	s_waitcnt vmcnt(0)
	s_barrier
	s_addc_u32 s49, s15, 0
	ds_read_b128 v[158:161], v7 offset:32768
	ds_read_b128 v[162:165], v6
	ds_read_b128 v[166:169], v7 offset:34816
	ds_read_b128 v[178:181], v6 offset:2048
	ds_read_b128 v[214:217], v7 offset:36864
	ds_read_b128 v[218:221], v7 offset:38912
	ds_read_b128 v[222:225], v6 offset:4096
	ds_read_b128 v[226:229], v6 offset:6144
	s_waitcnt lgkmcnt(6)
	v_mfma_f32_16x16x32_bf16 v[40:43], v[158:161], v[162:165], v[40:43]
	s_waitcnt lgkmcnt(5)
	v_mfma_f32_16x16x32_bf16 v[44:47], v[166:169], v[162:165], v[44:47]
	s_waitcnt lgkmcnt(4)
	v_mfma_f32_16x16x32_bf16 v[56:59], v[158:161], v[178:181], v[56:59]
	s_mov_b32 m0, s38
	v_mfma_f32_16x16x32_bf16 v[60:63], v[166:169], v[178:181], v[60:63]
	global_load_lds_dwordx4 v0, s[46:47]
	s_waitcnt lgkmcnt(3)
	v_mfma_f32_16x16x32_bf16 v[48:51], v[214:217], v[162:165], v[48:51]
	v_mfma_f32_16x16x32_bf16 v[64:67], v[214:217], v[178:181], v[64:67]
	s_waitcnt lgkmcnt(2)
	v_mfma_f32_16x16x32_bf16 v[174:177], v[218:221], v[162:165], v[174:177]
	ds_read_b128 v[162:165], v6 offset:8192
	v_mfma_f32_16x16x32_bf16 v[170:173], v[218:221], v[178:181], v[170:173]
	ds_read_b128 v[178:181], v6 offset:10240
	s_waitcnt lgkmcnt(3)
	s_mov_b32 m0, s37
	v_mfma_f32_16x16x32_bf16 v[72:75], v[158:161], v[222:225], v[72:75]
	global_load_lds_dwordx4 v0, s[48:49]
	v_mfma_f32_16x16x32_bf16 v[76:79], v[166:169], v[222:225], v[76:79]
	v_mfma_f32_16x16x32_bf16 v[80:83], v[214:217], v[222:225], v[80:83]
	v_mfma_f32_16x16x32_bf16 v[32:35], v[218:221], v[222:225], v[32:35]
	ds_read_b128 v[222:225], v6 offset:12288
	s_waitcnt lgkmcnt(3)
	v_mfma_f32_16x16x32_bf16 v[88:91], v[158:161], v[226:229], v[88:91]
	s_mov_b32 m0, s39
	v_mfma_f32_16x16x32_bf16 v[92:95], v[166:169], v[226:229], v[92:95]
	global_load_lds_dwordx4 v2, s[46:47]
	v_mfma_f32_16x16x32_bf16 v[96:99], v[214:217], v[226:229], v[96:99]
	v_mfma_f32_16x16x32_bf16 v[36:39], v[218:221], v[226:229], v[36:39]
	ds_read_b128 v[226:229], v6 offset:14336
	s_waitcnt lgkmcnt(3)
	v_mfma_f32_16x16x32_bf16 v[104:107], v[158:161], v[162:165], v[104:107]
	s_waitcnt lgkmcnt(2)
	v_mfma_f32_16x16x32_bf16 v[116:119], v[158:161], v[178:181], v[116:119]
	s_waitcnt lgkmcnt(1)
	s_mov_b32 m0, s40
	v_mfma_f32_16x16x32_bf16 v[128:131], v[158:161], v[222:225], v[128:131]
	global_load_lds_dwordx4 v2, s[48:49]
	s_waitcnt lgkmcnt(0)
	v_mfma_f32_16x16x32_bf16 v[100:103], v[158:161], v[226:229], v[100:103]
	ds_read_b128 v[158:161], v7 offset:33792
	v_mfma_f32_16x16x32_bf16 v[108:111], v[166:169], v[162:165], v[108:111]
	v_mfma_f32_16x16x32_bf16 v[120:123], v[166:169], v[178:181], v[120:123]
	v_mfma_f32_16x16x32_bf16 v[132:135], v[166:169], v[222:225], v[132:135]
	s_mov_b32 m0, s41
	v_mfma_f32_16x16x32_bf16 v[140:143], v[166:169], v[226:229], v[140:143]
	global_load_lds_dwordx4 v4, s[46:47]
	ds_read_b128 v[166:169], v6 offset:1024
	v_mfma_f32_16x16x32_bf16 v[112:115], v[214:217], v[162:165], v[112:115]
	v_mfma_f32_16x16x32_bf16 v[52:55], v[218:221], v[162:165], v[52:55]
	ds_read_b128 v[162:165], v7 offset:35840
	v_mfma_f32_16x16x32_bf16 v[124:127], v[214:217], v[178:181], v[124:127]
	v_mfma_f32_16x16x32_bf16 v[68:71], v[218:221], v[178:181], v[68:71]
	ds_read_b128 v[178:181], v6 offset:3072
	s_mov_b32 m0, s42
	v_mfma_f32_16x16x32_bf16 v[136:139], v[214:217], v[222:225], v[136:139]
	global_load_lds_dwordx4 v4, s[48:49]
	v_mfma_f32_16x16x32_bf16 v[84:87], v[218:221], v[222:225], v[84:87]
	ds_read_b128 v[222:225], v6 offset:5120
	v_mfma_f32_16x16x32_bf16 v[150:153], v[214:217], v[226:229], v[150:153]
	ds_read_b128 v[214:217], v7 offset:37888
	v_mfma_f32_16x16x32_bf16 v[154:157], v[218:221], v[226:229], v[154:157]
	ds_read_b128 v[218:221], v7 offset:39936
	ds_read_b128 v[226:229], v6 offset:7168
	s_waitcnt lgkmcnt(6)
	v_mfma_f32_16x16x32_bf16 v[40:43], v[158:161], v[166:169], v[40:43]
	s_waitcnt lgkmcnt(5)
	s_mov_b32 m0, s43
	v_mfma_f32_16x16x32_bf16 v[44:47], v[162:165], v[166:169], v[44:47]
	global_load_lds_dwordx4 v146, s[46:47]
	s_waitcnt lgkmcnt(4)
	v_mfma_f32_16x16x32_bf16 v[56:59], v[158:161], v[178:181], v[56:59]
	v_mfma_f32_16x16x32_bf16 v[60:63], v[162:165], v[178:181], v[60:63]
	s_waitcnt lgkmcnt(3)
	v_mfma_f32_16x16x32_bf16 v[72:75], v[158:161], v[222:225], v[72:75]
	v_mfma_f32_16x16x32_bf16 v[76:79], v[162:165], v[222:225], v[76:79]
	s_waitcnt lgkmcnt(2)
	s_mov_b32 m0, s44
	v_mfma_f32_16x16x32_bf16 v[48:51], v[214:217], v[166:169], v[48:51]
	global_load_lds_dwordx4 v146, s[48:49]
	s_waitcnt lgkmcnt(1)
	v_mfma_f32_16x16x32_bf16 v[174:177], v[218:221], v[166:169], v[174:177]
	ds_read_b128 v[166:169], v6 offset:9216
	v_mfma_f32_16x16x32_bf16 v[64:67], v[214:217], v[178:181], v[64:67]
	v_mfma_f32_16x16x32_bf16 v[170:173], v[218:221], v[178:181], v[170:173]
	ds_read_b128 v[178:181], v6 offset:11264
	v_mfma_f32_16x16x32_bf16 v[80:83], v[214:217], v[222:225], v[80:83]
	v_mfma_f32_16x16x32_bf16 v[32:35], v[218:221], v[222:225], v[32:35]
	ds_read_b128 v[222:225], v6 offset:13312
	s_waitcnt lgkmcnt(3)
	v_mfma_f32_16x16x32_bf16 v[88:91], v[158:161], v[226:229], v[88:91]
	v_mfma_f32_16x16x32_bf16 v[92:95], v[162:165], v[226:229], v[92:95]
	v_mfma_f32_16x16x32_bf16 v[96:99], v[214:217], v[226:229], v[96:99]
	v_mfma_f32_16x16x32_bf16 v[36:39], v[218:221], v[226:229], v[36:39]
	ds_read_b128 v[226:229], v6 offset:15360
	s_waitcnt lgkmcnt(3)
	v_mfma_f32_16x16x32_bf16 v[104:107], v[158:161], v[166:169], v[104:107]
	v_mfma_f32_16x16x32_bf16 v[108:111], v[162:165], v[166:169], v[108:111]
	v_mfma_f32_16x16x32_bf16 v[112:115], v[214:217], v[166:169], v[112:115]
	v_mfma_f32_16x16x32_bf16 v[52:55], v[218:221], v[166:169], v[52:55]
	s_waitcnt lgkmcnt(2)
	v_mfma_f32_16x16x32_bf16 v[116:119], v[158:161], v[178:181], v[116:119]
	v_mfma_f32_16x16x32_bf16 v[120:123], v[162:165], v[178:181], v[120:123]
	v_mfma_f32_16x16x32_bf16 v[124:127], v[214:217], v[178:181], v[124:127]
	v_mfma_f32_16x16x32_bf16 v[68:71], v[218:221], v[178:181], v[68:71]
	s_waitcnt lgkmcnt(1)
	v_mfma_f32_16x16x32_bf16 v[128:131], v[158:161], v[222:225], v[128:131]
	v_mfma_f32_16x16x32_bf16 v[132:135], v[162:165], v[222:225], v[132:135]
	v_mfma_f32_16x16x32_bf16 v[136:139], v[214:217], v[222:225], v[136:139]
	v_mfma_f32_16x16x32_bf16 v[84:87], v[218:221], v[222:225], v[84:87]
	s_waitcnt lgkmcnt(0)
	v_mfma_f32_16x16x32_bf16 v[100:103], v[158:161], v[226:229], v[100:103]
	v_mfma_f32_16x16x32_bf16 v[140:143], v[162:165], v[226:229], v[140:143]
	v_mfma_f32_16x16x32_bf16 v[150:153], v[214:217], v[226:229], v[150:153]
	v_mfma_f32_16x16x32_bf16 v[154:157], v[218:221], v[226:229], v[154:157]
	s_add_u32 s46, s0, 0x1e00
	s_addc_u32 s47, s1, 0
	s_add_u32 s48, s14, 0x1e00
	s_waitcnt vmcnt(0)
	s_barrier
	s_addc_u32 s49, s15, 0
	ds_read_b128 v[158:161], v8
	ds_read_b128 v[162:165], v12
	ds_read_b128 v[166:169], v9
	ds_read_b128 v[178:181], v13
	ds_read_b128 v[214:217], v11
	ds_read_b128 v[218:221], v10
	ds_read_b128 v[222:225], v14
	ds_read_b128 v[226:229], v15
	s_waitcnt lgkmcnt(6)
	v_mfma_f32_16x16x32_bf16 v[40:43], v[158:161], v[162:165], v[40:43]
	s_waitcnt lgkmcnt(5)
	v_mfma_f32_16x16x32_bf16 v[44:47], v[166:169], v[162:165], v[44:47]
	s_waitcnt lgkmcnt(4)
	v_mfma_f32_16x16x32_bf16 v[56:59], v[158:161], v[178:181], v[56:59]
	s_mov_b32 m0, s27
	v_mfma_f32_16x16x32_bf16 v[60:63], v[166:169], v[178:181], v[60:63]
	global_load_lds_dwordx4 v0, s[46:47]
	s_waitcnt lgkmcnt(3)
	v_mfma_f32_16x16x32_bf16 v[48:51], v[214:217], v[162:165], v[48:51]
	v_mfma_f32_16x16x32_bf16 v[64:67], v[214:217], v[178:181], v[64:67]
	s_waitcnt lgkmcnt(2)
	v_mfma_f32_16x16x32_bf16 v[174:177], v[218:221], v[162:165], v[174:177]
	ds_read_b128 v[162:165], v16
	v_mfma_f32_16x16x32_bf16 v[170:173], v[218:221], v[178:181], v[170:173]
	ds_read_b128 v[178:181], v17
	s_waitcnt lgkmcnt(3)
	s_mov_b32 m0, s28
	v_mfma_f32_16x16x32_bf16 v[72:75], v[158:161], v[222:225], v[72:75]
	global_load_lds_dwordx4 v0, s[48:49]
	v_mfma_f32_16x16x32_bf16 v[76:79], v[166:169], v[222:225], v[76:79]
	v_mfma_f32_16x16x32_bf16 v[80:83], v[214:217], v[222:225], v[80:83]
	v_mfma_f32_16x16x32_bf16 v[32:35], v[218:221], v[222:225], v[32:35]
	ds_read_b128 v[222:225], v18
	s_waitcnt lgkmcnt(3)
	v_mfma_f32_16x16x32_bf16 v[88:91], v[158:161], v[226:229], v[88:91]
	s_mov_b32 m0, s29
	v_mfma_f32_16x16x32_bf16 v[92:95], v[166:169], v[226:229], v[92:95]
	global_load_lds_dwordx4 v2, s[46:47]
	v_mfma_f32_16x16x32_bf16 v[96:99], v[214:217], v[226:229], v[96:99]
	v_mfma_f32_16x16x32_bf16 v[36:39], v[218:221], v[226:229], v[36:39]
	ds_read_b128 v[226:229], v19
	s_waitcnt lgkmcnt(3)
	v_mfma_f32_16x16x32_bf16 v[104:107], v[158:161], v[162:165], v[104:107]
	s_waitcnt lgkmcnt(2)
	v_mfma_f32_16x16x32_bf16 v[116:119], v[158:161], v[178:181], v[116:119]
	s_waitcnt lgkmcnt(1)
	s_mov_b32 m0, s30
	v_mfma_f32_16x16x32_bf16 v[128:131], v[158:161], v[222:225], v[128:131]
	global_load_lds_dwordx4 v2, s[48:49]
	s_waitcnt lgkmcnt(0)
	v_mfma_f32_16x16x32_bf16 v[100:103], v[158:161], v[226:229], v[100:103]
	ds_read_b128 v[158:161], v20
	v_mfma_f32_16x16x32_bf16 v[108:111], v[166:169], v[162:165], v[108:111]
	v_mfma_f32_16x16x32_bf16 v[120:123], v[166:169], v[178:181], v[120:123]
	v_mfma_f32_16x16x32_bf16 v[132:135], v[166:169], v[222:225], v[132:135]
	s_mov_b32 m0, s31
	v_mfma_f32_16x16x32_bf16 v[140:143], v[166:169], v[226:229], v[140:143]
	global_load_lds_dwordx4 v4, s[46:47]
	ds_read_b128 v[166:169], v24
	v_mfma_f32_16x16x32_bf16 v[112:115], v[214:217], v[162:165], v[112:115]
	v_mfma_f32_16x16x32_bf16 v[52:55], v[218:221], v[162:165], v[52:55]
	ds_read_b128 v[162:165], v21
	v_mfma_f32_16x16x32_bf16 v[124:127], v[214:217], v[178:181], v[124:127]
	v_mfma_f32_16x16x32_bf16 v[68:71], v[218:221], v[178:181], v[68:71]
	ds_read_b128 v[178:181], v25
	s_mov_b32 m0, s34
	v_mfma_f32_16x16x32_bf16 v[136:139], v[214:217], v[222:225], v[136:139]
	global_load_lds_dwordx4 v4, s[48:49]
	v_mfma_f32_16x16x32_bf16 v[84:87], v[218:221], v[222:225], v[84:87]
	ds_read_b128 v[222:225], v26
	v_mfma_f32_16x16x32_bf16 v[150:153], v[214:217], v[226:229], v[150:153]
	ds_read_b128 v[214:217], v23
	v_mfma_f32_16x16x32_bf16 v[154:157], v[218:221], v[226:229], v[154:157]
	ds_read_b128 v[218:221], v22
	ds_read_b128 v[226:229], v27
	s_waitcnt lgkmcnt(6)
	v_mfma_f32_16x16x32_bf16 v[40:43], v[158:161], v[166:169], v[40:43]
	s_waitcnt lgkmcnt(5)
	s_mov_b32 m0, s35
	v_mfma_f32_16x16x32_bf16 v[44:47], v[162:165], v[166:169], v[44:47]
	global_load_lds_dwordx4 v146, s[46:47]
	s_waitcnt lgkmcnt(4)
	v_mfma_f32_16x16x32_bf16 v[56:59], v[158:161], v[178:181], v[56:59]
	v_mfma_f32_16x16x32_bf16 v[60:63], v[162:165], v[178:181], v[60:63]
	s_waitcnt lgkmcnt(3)
	v_mfma_f32_16x16x32_bf16 v[72:75], v[158:161], v[222:225], v[72:75]
	v_mfma_f32_16x16x32_bf16 v[76:79], v[162:165], v[222:225], v[76:79]
	s_waitcnt lgkmcnt(2)
	s_mov_b32 m0, s36
	v_mfma_f32_16x16x32_bf16 v[48:51], v[214:217], v[166:169], v[48:51]
	global_load_lds_dwordx4 v146, s[48:49]
	s_waitcnt lgkmcnt(1)
	v_mfma_f32_16x16x32_bf16 v[174:177], v[218:221], v[166:169], v[174:177]
	ds_read_b128 v[166:169], v28
	v_mfma_f32_16x16x32_bf16 v[64:67], v[214:217], v[178:181], v[64:67]
	v_mfma_f32_16x16x32_bf16 v[170:173], v[218:221], v[178:181], v[170:173]
	ds_read_b128 v[178:181], v29
	v_mfma_f32_16x16x32_bf16 v[80:83], v[214:217], v[222:225], v[80:83]
	v_mfma_f32_16x16x32_bf16 v[32:35], v[218:221], v[222:225], v[32:35]
	ds_read_b128 v[222:225], v30
	s_waitcnt lgkmcnt(3)
	v_mfma_f32_16x16x32_bf16 v[88:91], v[158:161], v[226:229], v[88:91]
	v_mfma_f32_16x16x32_bf16 v[92:95], v[162:165], v[226:229], v[92:95]
	v_mfma_f32_16x16x32_bf16 v[96:99], v[214:217], v[226:229], v[96:99]
	v_mfma_f32_16x16x32_bf16 v[36:39], v[218:221], v[226:229], v[36:39]
	ds_read_b128 v[226:229], v31
	s_waitcnt lgkmcnt(3)
	v_mfma_f32_16x16x32_bf16 v[104:107], v[158:161], v[166:169], v[104:107]
	v_mfma_f32_16x16x32_bf16 v[108:111], v[162:165], v[166:169], v[108:111]
	v_mfma_f32_16x16x32_bf16 v[112:115], v[214:217], v[166:169], v[112:115]
	v_mfma_f32_16x16x32_bf16 v[52:55], v[218:221], v[166:169], v[52:55]
	s_waitcnt lgkmcnt(2)
	v_mfma_f32_16x16x32_bf16 v[116:119], v[158:161], v[178:181], v[116:119]
	v_mfma_f32_16x16x32_bf16 v[120:123], v[162:165], v[178:181], v[120:123]
	v_mfma_f32_16x16x32_bf16 v[124:127], v[214:217], v[178:181], v[124:127]
	v_mfma_f32_16x16x32_bf16 v[68:71], v[218:221], v[178:181], v[68:71]
	s_waitcnt lgkmcnt(1)
	v_mfma_f32_16x16x32_bf16 v[128:131], v[158:161], v[222:225], v[128:131]
	v_mfma_f32_16x16x32_bf16 v[132:135], v[162:165], v[222:225], v[132:135]
	v_mfma_f32_16x16x32_bf16 v[136:139], v[214:217], v[222:225], v[136:139]
	v_mfma_f32_16x16x32_bf16 v[84:87], v[218:221], v[222:225], v[84:87]
	s_waitcnt lgkmcnt(0)
	v_mfma_f32_16x16x32_bf16 v[100:103], v[158:161], v[226:229], v[100:103]
	v_mfma_f32_16x16x32_bf16 v[140:143], v[162:165], v[226:229], v[140:143]
	v_mfma_f32_16x16x32_bf16 v[150:153], v[214:217], v[226:229], v[150:153]
	v_mfma_f32_16x16x32_bf16 v[154:157], v[218:221], v[226:229], v[154:157]
	s_add_u32 s46, s0, 0x1e80
	s_addc_u32 s47, s1, 0
	s_add_u32 s48, s14, 0x1e80
	s_waitcnt vmcnt(0)
	s_barrier
	s_addc_u32 s49, s15, 0
	ds_read_b128 v[158:161], v7 offset:32768
	ds_read_b128 v[162:165], v6
	ds_read_b128 v[166:169], v7 offset:34816
	ds_read_b128 v[178:181], v6 offset:2048
	ds_read_b128 v[214:217], v7 offset:36864
	ds_read_b128 v[218:221], v7 offset:38912
	ds_read_b128 v[222:225], v6 offset:4096
	ds_read_b128 v[226:229], v6 offset:6144
	s_waitcnt lgkmcnt(6)
	v_mfma_f32_16x16x32_bf16 v[40:43], v[158:161], v[162:165], v[40:43]
	s_waitcnt lgkmcnt(5)
	v_mfma_f32_16x16x32_bf16 v[44:47], v[166:169], v[162:165], v[44:47]
	s_waitcnt lgkmcnt(4)
	v_mfma_f32_16x16x32_bf16 v[56:59], v[158:161], v[178:181], v[56:59]
	s_mov_b32 m0, s38
	v_mfma_f32_16x16x32_bf16 v[60:63], v[166:169], v[178:181], v[60:63]
	global_load_lds_dwordx4 v0, s[46:47]
	s_waitcnt lgkmcnt(3)
	v_mfma_f32_16x16x32_bf16 v[48:51], v[214:217], v[162:165], v[48:51]
	v_mfma_f32_16x16x32_bf16 v[64:67], v[214:217], v[178:181], v[64:67]
	s_waitcnt lgkmcnt(2)
	v_mfma_f32_16x16x32_bf16 v[174:177], v[218:221], v[162:165], v[174:177]
	ds_read_b128 v[162:165], v6 offset:8192
	v_mfma_f32_16x16x32_bf16 v[170:173], v[218:221], v[178:181], v[170:173]
	ds_read_b128 v[178:181], v6 offset:10240
	s_waitcnt lgkmcnt(3)
	s_mov_b32 m0, s37
	v_mfma_f32_16x16x32_bf16 v[72:75], v[158:161], v[222:225], v[72:75]
	global_load_lds_dwordx4 v0, s[48:49]
	v_mfma_f32_16x16x32_bf16 v[76:79], v[166:169], v[222:225], v[76:79]
	v_mfma_f32_16x16x32_bf16 v[80:83], v[214:217], v[222:225], v[80:83]
	v_mfma_f32_16x16x32_bf16 v[32:35], v[218:221], v[222:225], v[32:35]
	ds_read_b128 v[222:225], v6 offset:12288
	s_waitcnt lgkmcnt(3)
	v_mfma_f32_16x16x32_bf16 v[88:91], v[158:161], v[226:229], v[88:91]
	s_mov_b32 m0, s39
	v_mfma_f32_16x16x32_bf16 v[92:95], v[166:169], v[226:229], v[92:95]
	global_load_lds_dwordx4 v2, s[46:47]
	v_mfma_f32_16x16x32_bf16 v[96:99], v[214:217], v[226:229], v[96:99]
	v_mfma_f32_16x16x32_bf16 v[36:39], v[218:221], v[226:229], v[36:39]
	ds_read_b128 v[226:229], v6 offset:14336
	s_waitcnt lgkmcnt(3)
	v_mfma_f32_16x16x32_bf16 v[104:107], v[158:161], v[162:165], v[104:107]
	s_waitcnt lgkmcnt(2)
	v_mfma_f32_16x16x32_bf16 v[116:119], v[158:161], v[178:181], v[116:119]
	s_waitcnt lgkmcnt(1)
	s_mov_b32 m0, s40
	v_mfma_f32_16x16x32_bf16 v[128:131], v[158:161], v[222:225], v[128:131]
	global_load_lds_dwordx4 v2, s[48:49]
	s_waitcnt lgkmcnt(0)
	v_mfma_f32_16x16x32_bf16 v[100:103], v[158:161], v[226:229], v[100:103]
	ds_read_b128 v[158:161], v7 offset:33792
	v_mfma_f32_16x16x32_bf16 v[108:111], v[166:169], v[162:165], v[108:111]
	v_mfma_f32_16x16x32_bf16 v[120:123], v[166:169], v[178:181], v[120:123]
	v_mfma_f32_16x16x32_bf16 v[132:135], v[166:169], v[222:225], v[132:135]
	s_mov_b32 m0, s41
	v_mfma_f32_16x16x32_bf16 v[140:143], v[166:169], v[226:229], v[140:143]
	global_load_lds_dwordx4 v4, s[46:47]
	ds_read_b128 v[166:169], v6 offset:1024
	v_mfma_f32_16x16x32_bf16 v[112:115], v[214:217], v[162:165], v[112:115]
	v_mfma_f32_16x16x32_bf16 v[52:55], v[218:221], v[162:165], v[52:55]
	ds_read_b128 v[162:165], v7 offset:35840
	v_mfma_f32_16x16x32_bf16 v[124:127], v[214:217], v[178:181], v[124:127]
	v_mfma_f32_16x16x32_bf16 v[68:71], v[218:221], v[178:181], v[68:71]
	ds_read_b128 v[178:181], v6 offset:3072
	s_mov_b32 m0, s42
	v_mfma_f32_16x16x32_bf16 v[136:139], v[214:217], v[222:225], v[136:139]
	global_load_lds_dwordx4 v4, s[48:49]
	v_mfma_f32_16x16x32_bf16 v[84:87], v[218:221], v[222:225], v[84:87]
	ds_read_b128 v[222:225], v6 offset:5120
	v_mfma_f32_16x16x32_bf16 v[150:153], v[214:217], v[226:229], v[150:153]
	ds_read_b128 v[214:217], v7 offset:37888
	v_mfma_f32_16x16x32_bf16 v[154:157], v[218:221], v[226:229], v[154:157]
	ds_read_b128 v[218:221], v7 offset:39936
	ds_read_b128 v[226:229], v6 offset:7168
	s_waitcnt lgkmcnt(6)
	v_mfma_f32_16x16x32_bf16 v[40:43], v[158:161], v[166:169], v[40:43]
	s_waitcnt lgkmcnt(5)
	s_mov_b32 m0, s43
	v_mfma_f32_16x16x32_bf16 v[44:47], v[162:165], v[166:169], v[44:47]
	global_load_lds_dwordx4 v146, s[46:47]
	s_waitcnt lgkmcnt(4)
	v_mfma_f32_16x16x32_bf16 v[56:59], v[158:161], v[178:181], v[56:59]
	v_mfma_f32_16x16x32_bf16 v[60:63], v[162:165], v[178:181], v[60:63]
	s_waitcnt lgkmcnt(3)
	v_mfma_f32_16x16x32_bf16 v[72:75], v[158:161], v[222:225], v[72:75]
	v_mfma_f32_16x16x32_bf16 v[76:79], v[162:165], v[222:225], v[76:79]
	s_waitcnt lgkmcnt(2)
	s_mov_b32 m0, s44
	v_mfma_f32_16x16x32_bf16 v[48:51], v[214:217], v[166:169], v[48:51]
	global_load_lds_dwordx4 v146, s[48:49]
	s_waitcnt lgkmcnt(1)
	v_mfma_f32_16x16x32_bf16 v[174:177], v[218:221], v[166:169], v[174:177]
	ds_read_b128 v[166:169], v6 offset:9216
	v_mfma_f32_16x16x32_bf16 v[64:67], v[214:217], v[178:181], v[64:67]
	v_mfma_f32_16x16x32_bf16 v[170:173], v[218:221], v[178:181], v[170:173]
	ds_read_b128 v[178:181], v6 offset:11264
	v_mfma_f32_16x16x32_bf16 v[80:83], v[214:217], v[222:225], v[80:83]
	v_mfma_f32_16x16x32_bf16 v[32:35], v[218:221], v[222:225], v[32:35]
	ds_read_b128 v[222:225], v6 offset:13312
	s_waitcnt lgkmcnt(3)
	v_mfma_f32_16x16x32_bf16 v[88:91], v[158:161], v[226:229], v[88:91]
	v_mfma_f32_16x16x32_bf16 v[92:95], v[162:165], v[226:229], v[92:95]
	v_mfma_f32_16x16x32_bf16 v[96:99], v[214:217], v[226:229], v[96:99]
	v_mfma_f32_16x16x32_bf16 v[36:39], v[218:221], v[226:229], v[36:39]
	ds_read_b128 v[226:229], v6 offset:15360
	s_waitcnt lgkmcnt(3)
	v_mfma_f32_16x16x32_bf16 v[104:107], v[158:161], v[166:169], v[104:107]
	v_mfma_f32_16x16x32_bf16 v[108:111], v[162:165], v[166:169], v[108:111]
	v_mfma_f32_16x16x32_bf16 v[112:115], v[214:217], v[166:169], v[112:115]
	v_mfma_f32_16x16x32_bf16 v[52:55], v[218:221], v[166:169], v[52:55]
	s_waitcnt lgkmcnt(2)
	v_mfma_f32_16x16x32_bf16 v[116:119], v[158:161], v[178:181], v[116:119]
	v_mfma_f32_16x16x32_bf16 v[120:123], v[162:165], v[178:181], v[120:123]
	v_mfma_f32_16x16x32_bf16 v[124:127], v[214:217], v[178:181], v[124:127]
	v_mfma_f32_16x16x32_bf16 v[68:71], v[218:221], v[178:181], v[68:71]
	s_waitcnt lgkmcnt(1)
	v_mfma_f32_16x16x32_bf16 v[128:131], v[158:161], v[222:225], v[128:131]
	v_mfma_f32_16x16x32_bf16 v[132:135], v[162:165], v[222:225], v[132:135]
	v_mfma_f32_16x16x32_bf16 v[136:139], v[214:217], v[222:225], v[136:139]
	v_mfma_f32_16x16x32_bf16 v[84:87], v[218:221], v[222:225], v[84:87]
	s_waitcnt lgkmcnt(0)
	v_mfma_f32_16x16x32_bf16 v[100:103], v[158:161], v[226:229], v[100:103]
	v_mfma_f32_16x16x32_bf16 v[140:143], v[162:165], v[226:229], v[140:143]
	v_mfma_f32_16x16x32_bf16 v[150:153], v[214:217], v[226:229], v[150:153]
	v_mfma_f32_16x16x32_bf16 v[154:157], v[218:221], v[226:229], v[154:157]
	s_add_u32 s46, s0, 0x1f00
	s_addc_u32 s47, s1, 0
	s_add_u32 s48, s14, 0x1f00
	s_waitcnt vmcnt(0)
	s_barrier
	s_addc_u32 s49, s15, 0
	ds_read_b128 v[158:161], v8
	ds_read_b128 v[162:165], v12
	ds_read_b128 v[166:169], v9
	ds_read_b128 v[178:181], v13
	ds_read_b128 v[214:217], v11
	ds_read_b128 v[218:221], v10
	ds_read_b128 v[222:225], v14
	ds_read_b128 v[226:229], v15
	s_waitcnt lgkmcnt(6)
	v_mfma_f32_16x16x32_bf16 v[40:43], v[158:161], v[162:165], v[40:43]
	s_waitcnt lgkmcnt(5)
	v_mfma_f32_16x16x32_bf16 v[44:47], v[166:169], v[162:165], v[44:47]
	s_waitcnt lgkmcnt(4)
	v_mfma_f32_16x16x32_bf16 v[56:59], v[158:161], v[178:181], v[56:59]
	s_mov_b32 m0, s27
	v_mfma_f32_16x16x32_bf16 v[60:63], v[166:169], v[178:181], v[60:63]
	global_load_lds_dwordx4 v0, s[46:47]
	s_waitcnt lgkmcnt(3)
	v_mfma_f32_16x16x32_bf16 v[48:51], v[214:217], v[162:165], v[48:51]
	v_mfma_f32_16x16x32_bf16 v[64:67], v[214:217], v[178:181], v[64:67]
	s_waitcnt lgkmcnt(2)
	v_mfma_f32_16x16x32_bf16 v[174:177], v[218:221], v[162:165], v[174:177]
	ds_read_b128 v[162:165], v16
	v_mfma_f32_16x16x32_bf16 v[170:173], v[218:221], v[178:181], v[170:173]
	ds_read_b128 v[178:181], v17
	s_waitcnt lgkmcnt(3)
	s_mov_b32 m0, s28
	v_mfma_f32_16x16x32_bf16 v[72:75], v[158:161], v[222:225], v[72:75]
	global_load_lds_dwordx4 v0, s[48:49]
	v_mfma_f32_16x16x32_bf16 v[76:79], v[166:169], v[222:225], v[76:79]
	v_mfma_f32_16x16x32_bf16 v[80:83], v[214:217], v[222:225], v[80:83]
	v_mfma_f32_16x16x32_bf16 v[32:35], v[218:221], v[222:225], v[32:35]
	ds_read_b128 v[222:225], v18
	s_waitcnt lgkmcnt(3)
	v_mfma_f32_16x16x32_bf16 v[88:91], v[158:161], v[226:229], v[88:91]
	s_mov_b32 m0, s29
	v_mfma_f32_16x16x32_bf16 v[92:95], v[166:169], v[226:229], v[92:95]
	global_load_lds_dwordx4 v2, s[46:47]
	v_mfma_f32_16x16x32_bf16 v[96:99], v[214:217], v[226:229], v[96:99]
	v_mfma_f32_16x16x32_bf16 v[36:39], v[218:221], v[226:229], v[36:39]
	ds_read_b128 v[226:229], v19
	s_waitcnt lgkmcnt(3)
	v_mfma_f32_16x16x32_bf16 v[104:107], v[158:161], v[162:165], v[104:107]
	s_waitcnt lgkmcnt(2)
	v_mfma_f32_16x16x32_bf16 v[116:119], v[158:161], v[178:181], v[116:119]
	s_waitcnt lgkmcnt(1)
	s_mov_b32 m0, s30
	v_mfma_f32_16x16x32_bf16 v[128:131], v[158:161], v[222:225], v[128:131]
	global_load_lds_dwordx4 v2, s[48:49]
	s_waitcnt lgkmcnt(0)
	v_mfma_f32_16x16x32_bf16 v[100:103], v[158:161], v[226:229], v[100:103]
	ds_read_b128 v[158:161], v20
	v_mfma_f32_16x16x32_bf16 v[108:111], v[166:169], v[162:165], v[108:111]
	v_mfma_f32_16x16x32_bf16 v[120:123], v[166:169], v[178:181], v[120:123]
	v_mfma_f32_16x16x32_bf16 v[132:135], v[166:169], v[222:225], v[132:135]
	s_mov_b32 m0, s31
	v_mfma_f32_16x16x32_bf16 v[140:143], v[166:169], v[226:229], v[140:143]
	global_load_lds_dwordx4 v4, s[46:47]
	ds_read_b128 v[166:169], v24
	v_mfma_f32_16x16x32_bf16 v[112:115], v[214:217], v[162:165], v[112:115]
	v_mfma_f32_16x16x32_bf16 v[52:55], v[218:221], v[162:165], v[52:55]
	ds_read_b128 v[162:165], v21
	v_mfma_f32_16x16x32_bf16 v[124:127], v[214:217], v[178:181], v[124:127]
	v_mfma_f32_16x16x32_bf16 v[68:71], v[218:221], v[178:181], v[68:71]
	ds_read_b128 v[178:181], v25
	s_mov_b32 m0, s34
	v_mfma_f32_16x16x32_bf16 v[136:139], v[214:217], v[222:225], v[136:139]
	global_load_lds_dwordx4 v4, s[48:49]
	v_mfma_f32_16x16x32_bf16 v[84:87], v[218:221], v[222:225], v[84:87]
	ds_read_b128 v[222:225], v26
	v_mfma_f32_16x16x32_bf16 v[150:153], v[214:217], v[226:229], v[150:153]
	ds_read_b128 v[214:217], v23
	v_mfma_f32_16x16x32_bf16 v[154:157], v[218:221], v[226:229], v[154:157]
	ds_read_b128 v[218:221], v22
	ds_read_b128 v[226:229], v27
	s_waitcnt lgkmcnt(6)
	v_mfma_f32_16x16x32_bf16 v[40:43], v[158:161], v[166:169], v[40:43]
	s_waitcnt lgkmcnt(5)
	s_mov_b32 m0, s35
	v_mfma_f32_16x16x32_bf16 v[44:47], v[162:165], v[166:169], v[44:47]
	global_load_lds_dwordx4 v146, s[46:47]
	s_waitcnt lgkmcnt(4)
	v_mfma_f32_16x16x32_bf16 v[56:59], v[158:161], v[178:181], v[56:59]
	v_mfma_f32_16x16x32_bf16 v[60:63], v[162:165], v[178:181], v[60:63]
	s_waitcnt lgkmcnt(3)
	v_mfma_f32_16x16x32_bf16 v[72:75], v[158:161], v[222:225], v[72:75]
	v_mfma_f32_16x16x32_bf16 v[76:79], v[162:165], v[222:225], v[76:79]
	s_waitcnt lgkmcnt(2)
	s_mov_b32 m0, s36
	v_mfma_f32_16x16x32_bf16 v[48:51], v[214:217], v[166:169], v[48:51]
	global_load_lds_dwordx4 v146, s[48:49]
	s_waitcnt lgkmcnt(1)
	v_mfma_f32_16x16x32_bf16 v[174:177], v[218:221], v[166:169], v[174:177]
	ds_read_b128 v[166:169], v28
	v_mfma_f32_16x16x32_bf16 v[64:67], v[214:217], v[178:181], v[64:67]
	v_mfma_f32_16x16x32_bf16 v[170:173], v[218:221], v[178:181], v[170:173]
	ds_read_b128 v[178:181], v29
	v_mfma_f32_16x16x32_bf16 v[80:83], v[214:217], v[222:225], v[80:83]
	v_mfma_f32_16x16x32_bf16 v[32:35], v[218:221], v[222:225], v[32:35]
	ds_read_b128 v[222:225], v30
	s_waitcnt lgkmcnt(3)
	v_mfma_f32_16x16x32_bf16 v[88:91], v[158:161], v[226:229], v[88:91]
	v_mfma_f32_16x16x32_bf16 v[92:95], v[162:165], v[226:229], v[92:95]
	v_mfma_f32_16x16x32_bf16 v[96:99], v[214:217], v[226:229], v[96:99]
	v_mfma_f32_16x16x32_bf16 v[36:39], v[218:221], v[226:229], v[36:39]
	ds_read_b128 v[226:229], v31
	s_waitcnt lgkmcnt(3)
	v_mfma_f32_16x16x32_bf16 v[104:107], v[158:161], v[166:169], v[104:107]
	v_mfma_f32_16x16x32_bf16 v[108:111], v[162:165], v[166:169], v[108:111]
	v_mfma_f32_16x16x32_bf16 v[112:115], v[214:217], v[166:169], v[112:115]
	v_mfma_f32_16x16x32_bf16 v[52:55], v[218:221], v[166:169], v[52:55]
	s_waitcnt lgkmcnt(2)
	v_mfma_f32_16x16x32_bf16 v[116:119], v[158:161], v[178:181], v[116:119]
	v_mfma_f32_16x16x32_bf16 v[120:123], v[162:165], v[178:181], v[120:123]
	v_mfma_f32_16x16x32_bf16 v[124:127], v[214:217], v[178:181], v[124:127]
	v_mfma_f32_16x16x32_bf16 v[68:71], v[218:221], v[178:181], v[68:71]
	s_waitcnt lgkmcnt(1)
	v_mfma_f32_16x16x32_bf16 v[128:131], v[158:161], v[222:225], v[128:131]
	v_mfma_f32_16x16x32_bf16 v[132:135], v[162:165], v[222:225], v[132:135]
	v_mfma_f32_16x16x32_bf16 v[136:139], v[214:217], v[222:225], v[136:139]
	v_mfma_f32_16x16x32_bf16 v[84:87], v[218:221], v[222:225], v[84:87]
	s_waitcnt lgkmcnt(0)
	v_mfma_f32_16x16x32_bf16 v[100:103], v[158:161], v[226:229], v[100:103]
	v_mfma_f32_16x16x32_bf16 v[140:143], v[162:165], v[226:229], v[140:143]
	v_mfma_f32_16x16x32_bf16 v[150:153], v[214:217], v[226:229], v[150:153]
	v_mfma_f32_16x16x32_bf16 v[154:157], v[218:221], v[226:229], v[154:157]
	s_add_u32 s46, s0, 0x1f80
	s_addc_u32 s47, s1, 0
	s_add_u32 s48, s14, 0x1f80
	s_waitcnt vmcnt(0)
	s_barrier
	s_addc_u32 s49, s15, 0
	ds_read_b128 v[158:161], v7 offset:32768
	ds_read_b128 v[162:165], v6
	ds_read_b128 v[166:169], v7 offset:34816
	ds_read_b128 v[178:181], v6 offset:2048
	ds_read_b128 v[214:217], v7 offset:36864
	ds_read_b128 v[218:221], v7 offset:38912
	ds_read_b128 v[222:225], v6 offset:4096
	ds_read_b128 v[226:229], v6 offset:6144
	s_waitcnt lgkmcnt(6)
	v_mfma_f32_16x16x32_bf16 v[40:43], v[158:161], v[162:165], v[40:43]
	s_waitcnt lgkmcnt(5)
	v_mfma_f32_16x16x32_bf16 v[44:47], v[166:169], v[162:165], v[44:47]
	s_waitcnt lgkmcnt(4)
	v_mfma_f32_16x16x32_bf16 v[56:59], v[158:161], v[178:181], v[56:59]
	s_mov_b32 m0, s38
	v_mfma_f32_16x16x32_bf16 v[60:63], v[166:169], v[178:181], v[60:63]
	global_load_lds_dwordx4 v0, s[46:47]
	s_waitcnt lgkmcnt(3)
	v_mfma_f32_16x16x32_bf16 v[48:51], v[214:217], v[162:165], v[48:51]
	v_mfma_f32_16x16x32_bf16 v[64:67], v[214:217], v[178:181], v[64:67]
	s_waitcnt lgkmcnt(2)
	v_mfma_f32_16x16x32_bf16 v[174:177], v[218:221], v[162:165], v[174:177]
	ds_read_b128 v[162:165], v6 offset:8192
	v_mfma_f32_16x16x32_bf16 v[170:173], v[218:221], v[178:181], v[170:173]
	ds_read_b128 v[178:181], v6 offset:10240
	s_waitcnt lgkmcnt(3)
	s_mov_b32 m0, s37
	v_mfma_f32_16x16x32_bf16 v[72:75], v[158:161], v[222:225], v[72:75]
	global_load_lds_dwordx4 v0, s[48:49]
	v_mfma_f32_16x16x32_bf16 v[76:79], v[166:169], v[222:225], v[76:79]
	v_mfma_f32_16x16x32_bf16 v[80:83], v[214:217], v[222:225], v[80:83]
	v_mfma_f32_16x16x32_bf16 v[32:35], v[218:221], v[222:225], v[32:35]
	ds_read_b128 v[222:225], v6 offset:12288
	s_waitcnt lgkmcnt(3)
	v_mfma_f32_16x16x32_bf16 v[88:91], v[158:161], v[226:229], v[88:91]
	s_mov_b32 m0, s39
	v_mfma_f32_16x16x32_bf16 v[92:95], v[166:169], v[226:229], v[92:95]
	global_load_lds_dwordx4 v2, s[46:47]
	v_mfma_f32_16x16x32_bf16 v[96:99], v[214:217], v[226:229], v[96:99]
	v_mfma_f32_16x16x32_bf16 v[36:39], v[218:221], v[226:229], v[36:39]
	ds_read_b128 v[226:229], v6 offset:14336
	s_waitcnt lgkmcnt(3)
	v_mfma_f32_16x16x32_bf16 v[104:107], v[158:161], v[162:165], v[104:107]
	s_waitcnt lgkmcnt(2)
	v_mfma_f32_16x16x32_bf16 v[116:119], v[158:161], v[178:181], v[116:119]
	s_waitcnt lgkmcnt(1)
	s_mov_b32 m0, s40
	v_mfma_f32_16x16x32_bf16 v[128:131], v[158:161], v[222:225], v[128:131]
	global_load_lds_dwordx4 v2, s[48:49]
	s_waitcnt lgkmcnt(0)
	v_mfma_f32_16x16x32_bf16 v[100:103], v[158:161], v[226:229], v[100:103]
	ds_read_b128 v[158:161], v7 offset:33792
	v_mfma_f32_16x16x32_bf16 v[108:111], v[166:169], v[162:165], v[108:111]
	v_mfma_f32_16x16x32_bf16 v[120:123], v[166:169], v[178:181], v[120:123]
	v_mfma_f32_16x16x32_bf16 v[132:135], v[166:169], v[222:225], v[132:135]
	s_mov_b32 m0, s41
	v_mfma_f32_16x16x32_bf16 v[140:143], v[166:169], v[226:229], v[140:143]
	global_load_lds_dwordx4 v4, s[46:47]
	ds_read_b128 v[166:169], v6 offset:1024
	v_mfma_f32_16x16x32_bf16 v[112:115], v[214:217], v[162:165], v[112:115]
	v_mfma_f32_16x16x32_bf16 v[52:55], v[218:221], v[162:165], v[52:55]
	ds_read_b128 v[162:165], v7 offset:35840
	v_mfma_f32_16x16x32_bf16 v[124:127], v[214:217], v[178:181], v[124:127]
	v_mfma_f32_16x16x32_bf16 v[68:71], v[218:221], v[178:181], v[68:71]
	ds_read_b128 v[178:181], v6 offset:3072
	s_mov_b32 m0, s42
	v_mfma_f32_16x16x32_bf16 v[136:139], v[214:217], v[222:225], v[136:139]
	global_load_lds_dwordx4 v4, s[48:49]
	v_mfma_f32_16x16x32_bf16 v[84:87], v[218:221], v[222:225], v[84:87]
	ds_read_b128 v[222:225], v6 offset:5120
	v_mfma_f32_16x16x32_bf16 v[150:153], v[214:217], v[226:229], v[150:153]
	ds_read_b128 v[214:217], v7 offset:37888
	v_mfma_f32_16x16x32_bf16 v[154:157], v[218:221], v[226:229], v[154:157]
	ds_read_b128 v[218:221], v7 offset:39936
	ds_read_b128 v[226:229], v6 offset:7168
	s_waitcnt lgkmcnt(6)
	v_mfma_f32_16x16x32_bf16 v[40:43], v[158:161], v[166:169], v[40:43]
	s_waitcnt lgkmcnt(5)
	s_mov_b32 m0, s43
	v_mfma_f32_16x16x32_bf16 v[44:47], v[162:165], v[166:169], v[44:47]
	global_load_lds_dwordx4 v146, s[46:47]
	s_waitcnt lgkmcnt(4)
	v_mfma_f32_16x16x32_bf16 v[56:59], v[158:161], v[178:181], v[56:59]
	v_mfma_f32_16x16x32_bf16 v[60:63], v[162:165], v[178:181], v[60:63]
	s_waitcnt lgkmcnt(3)
	v_mfma_f32_16x16x32_bf16 v[72:75], v[158:161], v[222:225], v[72:75]
	v_mfma_f32_16x16x32_bf16 v[76:79], v[162:165], v[222:225], v[76:79]
	s_waitcnt lgkmcnt(2)
	s_mov_b32 m0, s44
	v_mfma_f32_16x16x32_bf16 v[48:51], v[214:217], v[166:169], v[48:51]
	global_load_lds_dwordx4 v146, s[48:49]
	s_waitcnt lgkmcnt(1)
	v_mfma_f32_16x16x32_bf16 v[174:177], v[218:221], v[166:169], v[174:177]
	ds_read_b128 v[166:169], v6 offset:9216
	v_mfma_f32_16x16x32_bf16 v[64:67], v[214:217], v[178:181], v[64:67]
	v_mfma_f32_16x16x32_bf16 v[170:173], v[218:221], v[178:181], v[170:173]
	ds_read_b128 v[178:181], v6 offset:11264
	v_mfma_f32_16x16x32_bf16 v[80:83], v[214:217], v[222:225], v[80:83]
	v_mfma_f32_16x16x32_bf16 v[32:35], v[218:221], v[222:225], v[32:35]
	ds_read_b128 v[222:225], v6 offset:13312
	s_waitcnt lgkmcnt(3)
	v_mfma_f32_16x16x32_bf16 v[88:91], v[158:161], v[226:229], v[88:91]
	v_mfma_f32_16x16x32_bf16 v[92:95], v[162:165], v[226:229], v[92:95]
	v_mfma_f32_16x16x32_bf16 v[96:99], v[214:217], v[226:229], v[96:99]
	v_mfma_f32_16x16x32_bf16 v[36:39], v[218:221], v[226:229], v[36:39]
	ds_read_b128 v[226:229], v6 offset:15360
	s_waitcnt lgkmcnt(3)
	v_mfma_f32_16x16x32_bf16 v[104:107], v[158:161], v[166:169], v[104:107]
	v_mfma_f32_16x16x32_bf16 v[108:111], v[162:165], v[166:169], v[108:111]
	v_mfma_f32_16x16x32_bf16 v[112:115], v[214:217], v[166:169], v[112:115]
	v_mfma_f32_16x16x32_bf16 v[52:55], v[218:221], v[166:169], v[52:55]
	s_waitcnt lgkmcnt(2)
	v_mfma_f32_16x16x32_bf16 v[116:119], v[158:161], v[178:181], v[116:119]
	v_mfma_f32_16x16x32_bf16 v[120:123], v[162:165], v[178:181], v[120:123]
	v_mfma_f32_16x16x32_bf16 v[124:127], v[214:217], v[178:181], v[124:127]
	v_mfma_f32_16x16x32_bf16 v[68:71], v[218:221], v[178:181], v[68:71]
	s_waitcnt lgkmcnt(1)
	v_mfma_f32_16x16x32_bf16 v[128:131], v[158:161], v[222:225], v[128:131]
	v_mfma_f32_16x16x32_bf16 v[132:135], v[162:165], v[222:225], v[132:135]
	v_mfma_f32_16x16x32_bf16 v[136:139], v[214:217], v[222:225], v[136:139]
	v_mfma_f32_16x16x32_bf16 v[84:87], v[218:221], v[222:225], v[84:87]
	s_waitcnt lgkmcnt(0)
	v_mfma_f32_16x16x32_bf16 v[100:103], v[158:161], v[226:229], v[100:103]
	v_mfma_f32_16x16x32_bf16 v[140:143], v[162:165], v[226:229], v[140:143]
	v_mfma_f32_16x16x32_bf16 v[150:153], v[214:217], v[226:229], v[150:153]
	v_mfma_f32_16x16x32_bf16 v[154:157], v[218:221], v[226:229], v[154:157]
	s_add_u32 s46, s0, 0x2000
	s_addc_u32 s47, s1, 0
	s_add_u32 s48, s14, 0x2000
	s_waitcnt vmcnt(0)
	s_barrier
	s_addc_u32 s49, s15, 0
	ds_read_b128 v[158:161], v8
	ds_read_b128 v[162:165], v12
	ds_read_b128 v[166:169], v9
	ds_read_b128 v[178:181], v13
	ds_read_b128 v[214:217], v11
	ds_read_b128 v[218:221], v10
	ds_read_b128 v[222:225], v14
	ds_read_b128 v[226:229], v15
	s_waitcnt lgkmcnt(6)
	v_mfma_f32_16x16x32_bf16 v[40:43], v[158:161], v[162:165], v[40:43]
	s_waitcnt lgkmcnt(5)
	v_mfma_f32_16x16x32_bf16 v[44:47], v[166:169], v[162:165], v[44:47]
	s_waitcnt lgkmcnt(4)
	v_mfma_f32_16x16x32_bf16 v[56:59], v[158:161], v[178:181], v[56:59]
	s_mov_b32 m0, s27
	v_mfma_f32_16x16x32_bf16 v[60:63], v[166:169], v[178:181], v[60:63]
	global_load_lds_dwordx4 v0, s[46:47]
	s_waitcnt lgkmcnt(3)
	v_mfma_f32_16x16x32_bf16 v[48:51], v[214:217], v[162:165], v[48:51]
	v_mfma_f32_16x16x32_bf16 v[64:67], v[214:217], v[178:181], v[64:67]
	s_waitcnt lgkmcnt(2)
	v_mfma_f32_16x16x32_bf16 v[174:177], v[218:221], v[162:165], v[174:177]
	ds_read_b128 v[162:165], v16
	v_mfma_f32_16x16x32_bf16 v[170:173], v[218:221], v[178:181], v[170:173]
	ds_read_b128 v[178:181], v17
	s_waitcnt lgkmcnt(3)
	s_mov_b32 m0, s28
	v_mfma_f32_16x16x32_bf16 v[72:75], v[158:161], v[222:225], v[72:75]
	global_load_lds_dwordx4 v0, s[48:49]
	v_mfma_f32_16x16x32_bf16 v[76:79], v[166:169], v[222:225], v[76:79]
	v_mfma_f32_16x16x32_bf16 v[80:83], v[214:217], v[222:225], v[80:83]
	v_mfma_f32_16x16x32_bf16 v[32:35], v[218:221], v[222:225], v[32:35]
	ds_read_b128 v[222:225], v18
	s_waitcnt lgkmcnt(3)
	v_mfma_f32_16x16x32_bf16 v[88:91], v[158:161], v[226:229], v[88:91]
	s_mov_b32 m0, s29
	v_mfma_f32_16x16x32_bf16 v[92:95], v[166:169], v[226:229], v[92:95]
	global_load_lds_dwordx4 v2, s[46:47]
	v_mfma_f32_16x16x32_bf16 v[96:99], v[214:217], v[226:229], v[96:99]
	v_mfma_f32_16x16x32_bf16 v[36:39], v[218:221], v[226:229], v[36:39]
	ds_read_b128 v[226:229], v19
	s_waitcnt lgkmcnt(3)
	v_mfma_f32_16x16x32_bf16 v[104:107], v[158:161], v[162:165], v[104:107]
	s_waitcnt lgkmcnt(2)
	v_mfma_f32_16x16x32_bf16 v[116:119], v[158:161], v[178:181], v[116:119]
	s_waitcnt lgkmcnt(1)
	s_mov_b32 m0, s30
	v_mfma_f32_16x16x32_bf16 v[128:131], v[158:161], v[222:225], v[128:131]
	global_load_lds_dwordx4 v2, s[48:49]
	s_waitcnt lgkmcnt(0)
	v_mfma_f32_16x16x32_bf16 v[100:103], v[158:161], v[226:229], v[100:103]
	ds_read_b128 v[158:161], v20
	v_mfma_f32_16x16x32_bf16 v[108:111], v[166:169], v[162:165], v[108:111]
	v_mfma_f32_16x16x32_bf16 v[120:123], v[166:169], v[178:181], v[120:123]
	v_mfma_f32_16x16x32_bf16 v[132:135], v[166:169], v[222:225], v[132:135]
	s_mov_b32 m0, s31
	v_mfma_f32_16x16x32_bf16 v[140:143], v[166:169], v[226:229], v[140:143]
	global_load_lds_dwordx4 v4, s[46:47]
	ds_read_b128 v[166:169], v24
	v_mfma_f32_16x16x32_bf16 v[112:115], v[214:217], v[162:165], v[112:115]
	v_mfma_f32_16x16x32_bf16 v[52:55], v[218:221], v[162:165], v[52:55]
	ds_read_b128 v[162:165], v21
	v_mfma_f32_16x16x32_bf16 v[124:127], v[214:217], v[178:181], v[124:127]
	v_mfma_f32_16x16x32_bf16 v[68:71], v[218:221], v[178:181], v[68:71]
	ds_read_b128 v[178:181], v25
	s_mov_b32 m0, s34
	v_mfma_f32_16x16x32_bf16 v[136:139], v[214:217], v[222:225], v[136:139]
	global_load_lds_dwordx4 v4, s[48:49]
	v_mfma_f32_16x16x32_bf16 v[84:87], v[218:221], v[222:225], v[84:87]
	ds_read_b128 v[222:225], v26
	v_mfma_f32_16x16x32_bf16 v[150:153], v[214:217], v[226:229], v[150:153]
	ds_read_b128 v[214:217], v23
	v_mfma_f32_16x16x32_bf16 v[154:157], v[218:221], v[226:229], v[154:157]
	ds_read_b128 v[218:221], v22
	ds_read_b128 v[226:229], v27
	s_waitcnt lgkmcnt(6)
	v_mfma_f32_16x16x32_bf16 v[40:43], v[158:161], v[166:169], v[40:43]
	s_waitcnt lgkmcnt(5)
	s_mov_b32 m0, s35
	v_mfma_f32_16x16x32_bf16 v[44:47], v[162:165], v[166:169], v[44:47]
	global_load_lds_dwordx4 v146, s[46:47]
	s_waitcnt lgkmcnt(4)
	v_mfma_f32_16x16x32_bf16 v[56:59], v[158:161], v[178:181], v[56:59]
	v_mfma_f32_16x16x32_bf16 v[60:63], v[162:165], v[178:181], v[60:63]
	s_waitcnt lgkmcnt(3)
	v_mfma_f32_16x16x32_bf16 v[72:75], v[158:161], v[222:225], v[72:75]
	v_mfma_f32_16x16x32_bf16 v[76:79], v[162:165], v[222:225], v[76:79]
	s_waitcnt lgkmcnt(2)
	s_mov_b32 m0, s36
	v_mfma_f32_16x16x32_bf16 v[48:51], v[214:217], v[166:169], v[48:51]
	global_load_lds_dwordx4 v146, s[48:49]
	s_waitcnt lgkmcnt(1)
	v_mfma_f32_16x16x32_bf16 v[174:177], v[218:221], v[166:169], v[174:177]
	ds_read_b128 v[166:169], v28
	v_mfma_f32_16x16x32_bf16 v[64:67], v[214:217], v[178:181], v[64:67]
	v_mfma_f32_16x16x32_bf16 v[170:173], v[218:221], v[178:181], v[170:173]
	ds_read_b128 v[178:181], v29
	v_mfma_f32_16x16x32_bf16 v[80:83], v[214:217], v[222:225], v[80:83]
	v_mfma_f32_16x16x32_bf16 v[32:35], v[218:221], v[222:225], v[32:35]
	ds_read_b128 v[222:225], v30
	s_waitcnt lgkmcnt(3)
	v_mfma_f32_16x16x32_bf16 v[88:91], v[158:161], v[226:229], v[88:91]
	v_mfma_f32_16x16x32_bf16 v[92:95], v[162:165], v[226:229], v[92:95]
	v_mfma_f32_16x16x32_bf16 v[96:99], v[214:217], v[226:229], v[96:99]
	v_mfma_f32_16x16x32_bf16 v[36:39], v[218:221], v[226:229], v[36:39]
	ds_read_b128 v[226:229], v31
	s_waitcnt lgkmcnt(3)
	v_mfma_f32_16x16x32_bf16 v[104:107], v[158:161], v[166:169], v[104:107]
	v_mfma_f32_16x16x32_bf16 v[108:111], v[162:165], v[166:169], v[108:111]
	v_mfma_f32_16x16x32_bf16 v[112:115], v[214:217], v[166:169], v[112:115]
	v_mfma_f32_16x16x32_bf16 v[52:55], v[218:221], v[166:169], v[52:55]
	s_waitcnt lgkmcnt(2)
	v_mfma_f32_16x16x32_bf16 v[116:119], v[158:161], v[178:181], v[116:119]
	v_mfma_f32_16x16x32_bf16 v[120:123], v[162:165], v[178:181], v[120:123]
	v_mfma_f32_16x16x32_bf16 v[124:127], v[214:217], v[178:181], v[124:127]
	v_mfma_f32_16x16x32_bf16 v[68:71], v[218:221], v[178:181], v[68:71]
	s_waitcnt lgkmcnt(1)
	v_mfma_f32_16x16x32_bf16 v[128:131], v[158:161], v[222:225], v[128:131]
	v_mfma_f32_16x16x32_bf16 v[132:135], v[162:165], v[222:225], v[132:135]
	v_mfma_f32_16x16x32_bf16 v[136:139], v[214:217], v[222:225], v[136:139]
	v_mfma_f32_16x16x32_bf16 v[84:87], v[218:221], v[222:225], v[84:87]
	s_waitcnt lgkmcnt(0)
	v_mfma_f32_16x16x32_bf16 v[100:103], v[158:161], v[226:229], v[100:103]
	v_mfma_f32_16x16x32_bf16 v[140:143], v[162:165], v[226:229], v[140:143]
	v_mfma_f32_16x16x32_bf16 v[150:153], v[214:217], v[226:229], v[150:153]
	v_mfma_f32_16x16x32_bf16 v[154:157], v[218:221], v[226:229], v[154:157]
	s_add_u32 s46, s0, 0x2080
	s_addc_u32 s47, s1, 0
	s_add_u32 s48, s14, 0x2080
	s_waitcnt vmcnt(0)
	s_barrier
	s_addc_u32 s49, s15, 0
	ds_read_b128 v[158:161], v7 offset:32768
	ds_read_b128 v[162:165], v6
	ds_read_b128 v[166:169], v7 offset:34816
	ds_read_b128 v[178:181], v6 offset:2048
	ds_read_b128 v[214:217], v7 offset:36864
	ds_read_b128 v[218:221], v7 offset:38912
	ds_read_b128 v[222:225], v6 offset:4096
	ds_read_b128 v[226:229], v6 offset:6144
	s_waitcnt lgkmcnt(6)
	v_mfma_f32_16x16x32_bf16 v[40:43], v[158:161], v[162:165], v[40:43]
	s_waitcnt lgkmcnt(5)
	v_mfma_f32_16x16x32_bf16 v[44:47], v[166:169], v[162:165], v[44:47]
	s_waitcnt lgkmcnt(4)
	v_mfma_f32_16x16x32_bf16 v[56:59], v[158:161], v[178:181], v[56:59]
	s_mov_b32 m0, s38
	v_mfma_f32_16x16x32_bf16 v[60:63], v[166:169], v[178:181], v[60:63]
	global_load_lds_dwordx4 v0, s[46:47]
	s_waitcnt lgkmcnt(3)
	v_mfma_f32_16x16x32_bf16 v[48:51], v[214:217], v[162:165], v[48:51]
	v_mfma_f32_16x16x32_bf16 v[64:67], v[214:217], v[178:181], v[64:67]
	s_waitcnt lgkmcnt(2)
	v_mfma_f32_16x16x32_bf16 v[174:177], v[218:221], v[162:165], v[174:177]
	ds_read_b128 v[162:165], v6 offset:8192
	v_mfma_f32_16x16x32_bf16 v[170:173], v[218:221], v[178:181], v[170:173]
	ds_read_b128 v[178:181], v6 offset:10240
	s_waitcnt lgkmcnt(3)
	s_mov_b32 m0, s37
	v_mfma_f32_16x16x32_bf16 v[72:75], v[158:161], v[222:225], v[72:75]
	global_load_lds_dwordx4 v0, s[48:49]
	v_mfma_f32_16x16x32_bf16 v[76:79], v[166:169], v[222:225], v[76:79]
	v_mfma_f32_16x16x32_bf16 v[80:83], v[214:217], v[222:225], v[80:83]
	v_mfma_f32_16x16x32_bf16 v[32:35], v[218:221], v[222:225], v[32:35]
	ds_read_b128 v[222:225], v6 offset:12288
	s_waitcnt lgkmcnt(3)
	v_mfma_f32_16x16x32_bf16 v[88:91], v[158:161], v[226:229], v[88:91]
	s_mov_b32 m0, s39
	v_mfma_f32_16x16x32_bf16 v[92:95], v[166:169], v[226:229], v[92:95]
	global_load_lds_dwordx4 v2, s[46:47]
	v_mfma_f32_16x16x32_bf16 v[96:99], v[214:217], v[226:229], v[96:99]
	v_mfma_f32_16x16x32_bf16 v[36:39], v[218:221], v[226:229], v[36:39]
	ds_read_b128 v[226:229], v6 offset:14336
	s_waitcnt lgkmcnt(3)
	v_mfma_f32_16x16x32_bf16 v[104:107], v[158:161], v[162:165], v[104:107]
	s_waitcnt lgkmcnt(2)
	v_mfma_f32_16x16x32_bf16 v[116:119], v[158:161], v[178:181], v[116:119]
	s_waitcnt lgkmcnt(1)
	s_mov_b32 m0, s40
	v_mfma_f32_16x16x32_bf16 v[128:131], v[158:161], v[222:225], v[128:131]
	global_load_lds_dwordx4 v2, s[48:49]
	s_waitcnt lgkmcnt(0)
	v_mfma_f32_16x16x32_bf16 v[100:103], v[158:161], v[226:229], v[100:103]
	ds_read_b128 v[158:161], v7 offset:33792
	v_mfma_f32_16x16x32_bf16 v[108:111], v[166:169], v[162:165], v[108:111]
	v_mfma_f32_16x16x32_bf16 v[120:123], v[166:169], v[178:181], v[120:123]
	v_mfma_f32_16x16x32_bf16 v[132:135], v[166:169], v[222:225], v[132:135]
	s_mov_b32 m0, s41
	v_mfma_f32_16x16x32_bf16 v[140:143], v[166:169], v[226:229], v[140:143]
	global_load_lds_dwordx4 v4, s[46:47]
	ds_read_b128 v[166:169], v6 offset:1024
	v_mfma_f32_16x16x32_bf16 v[112:115], v[214:217], v[162:165], v[112:115]
	v_mfma_f32_16x16x32_bf16 v[52:55], v[218:221], v[162:165], v[52:55]
	ds_read_b128 v[162:165], v7 offset:35840
	v_mfma_f32_16x16x32_bf16 v[124:127], v[214:217], v[178:181], v[124:127]
	v_mfma_f32_16x16x32_bf16 v[68:71], v[218:221], v[178:181], v[68:71]
	ds_read_b128 v[178:181], v6 offset:3072
	s_mov_b32 m0, s42
	v_mfma_f32_16x16x32_bf16 v[136:139], v[214:217], v[222:225], v[136:139]
	global_load_lds_dwordx4 v4, s[48:49]
	v_mfma_f32_16x16x32_bf16 v[84:87], v[218:221], v[222:225], v[84:87]
	ds_read_b128 v[222:225], v6 offset:5120
	v_mfma_f32_16x16x32_bf16 v[150:153], v[214:217], v[226:229], v[150:153]
	ds_read_b128 v[214:217], v7 offset:37888
	v_mfma_f32_16x16x32_bf16 v[154:157], v[218:221], v[226:229], v[154:157]
	ds_read_b128 v[218:221], v7 offset:39936
	ds_read_b128 v[226:229], v6 offset:7168
	s_waitcnt lgkmcnt(6)
	v_mfma_f32_16x16x32_bf16 v[40:43], v[158:161], v[166:169], v[40:43]
	s_waitcnt lgkmcnt(5)
	s_mov_b32 m0, s43
	v_mfma_f32_16x16x32_bf16 v[44:47], v[162:165], v[166:169], v[44:47]
	global_load_lds_dwordx4 v146, s[46:47]
	s_waitcnt lgkmcnt(4)
	v_mfma_f32_16x16x32_bf16 v[56:59], v[158:161], v[178:181], v[56:59]
	v_mfma_f32_16x16x32_bf16 v[60:63], v[162:165], v[178:181], v[60:63]
	s_waitcnt lgkmcnt(3)
	v_mfma_f32_16x16x32_bf16 v[72:75], v[158:161], v[222:225], v[72:75]
	v_mfma_f32_16x16x32_bf16 v[76:79], v[162:165], v[222:225], v[76:79]
	s_waitcnt lgkmcnt(2)
	s_mov_b32 m0, s44
	v_mfma_f32_16x16x32_bf16 v[48:51], v[214:217], v[166:169], v[48:51]
	global_load_lds_dwordx4 v146, s[48:49]
	s_waitcnt lgkmcnt(1)
	v_mfma_f32_16x16x32_bf16 v[174:177], v[218:221], v[166:169], v[174:177]
	ds_read_b128 v[166:169], v6 offset:9216
	v_mfma_f32_16x16x32_bf16 v[64:67], v[214:217], v[178:181], v[64:67]
	v_mfma_f32_16x16x32_bf16 v[170:173], v[218:221], v[178:181], v[170:173]
	ds_read_b128 v[178:181], v6 offset:11264
	v_mfma_f32_16x16x32_bf16 v[80:83], v[214:217], v[222:225], v[80:83]
	v_mfma_f32_16x16x32_bf16 v[32:35], v[218:221], v[222:225], v[32:35]
	ds_read_b128 v[222:225], v6 offset:13312
	s_waitcnt lgkmcnt(3)
	v_mfma_f32_16x16x32_bf16 v[88:91], v[158:161], v[226:229], v[88:91]
	v_mfma_f32_16x16x32_bf16 v[92:95], v[162:165], v[226:229], v[92:95]
	v_mfma_f32_16x16x32_bf16 v[96:99], v[214:217], v[226:229], v[96:99]
	v_mfma_f32_16x16x32_bf16 v[36:39], v[218:221], v[226:229], v[36:39]
	ds_read_b128 v[226:229], v6 offset:15360
	s_waitcnt lgkmcnt(3)
	v_mfma_f32_16x16x32_bf16 v[104:107], v[158:161], v[166:169], v[104:107]
	v_mfma_f32_16x16x32_bf16 v[108:111], v[162:165], v[166:169], v[108:111]
	v_mfma_f32_16x16x32_bf16 v[112:115], v[214:217], v[166:169], v[112:115]
	v_mfma_f32_16x16x32_bf16 v[52:55], v[218:221], v[166:169], v[52:55]
	s_waitcnt lgkmcnt(2)
	v_mfma_f32_16x16x32_bf16 v[116:119], v[158:161], v[178:181], v[116:119]
	v_mfma_f32_16x16x32_bf16 v[120:123], v[162:165], v[178:181], v[120:123]
	v_mfma_f32_16x16x32_bf16 v[124:127], v[214:217], v[178:181], v[124:127]
	v_mfma_f32_16x16x32_bf16 v[68:71], v[218:221], v[178:181], v[68:71]
	s_waitcnt lgkmcnt(1)
	v_mfma_f32_16x16x32_bf16 v[128:131], v[158:161], v[222:225], v[128:131]
	v_mfma_f32_16x16x32_bf16 v[132:135], v[162:165], v[222:225], v[132:135]
	v_mfma_f32_16x16x32_bf16 v[136:139], v[214:217], v[222:225], v[136:139]
	v_mfma_f32_16x16x32_bf16 v[84:87], v[218:221], v[222:225], v[84:87]
	s_waitcnt lgkmcnt(0)
	v_mfma_f32_16x16x32_bf16 v[100:103], v[158:161], v[226:229], v[100:103]
	v_mfma_f32_16x16x32_bf16 v[140:143], v[162:165], v[226:229], v[140:143]
	v_mfma_f32_16x16x32_bf16 v[150:153], v[214:217], v[226:229], v[150:153]
	v_mfma_f32_16x16x32_bf16 v[154:157], v[218:221], v[226:229], v[154:157]
	s_add_u32 s46, s0, 0x2100
	s_addc_u32 s47, s1, 0
	s_add_u32 s48, s14, 0x2100
	s_waitcnt vmcnt(0)
	s_barrier
	s_addc_u32 s49, s15, 0
	ds_read_b128 v[158:161], v8
	ds_read_b128 v[162:165], v12
	ds_read_b128 v[166:169], v9
	ds_read_b128 v[178:181], v13
	ds_read_b128 v[214:217], v11
	ds_read_b128 v[218:221], v10
	ds_read_b128 v[222:225], v14
	ds_read_b128 v[226:229], v15
	s_waitcnt lgkmcnt(6)
	v_mfma_f32_16x16x32_bf16 v[40:43], v[158:161], v[162:165], v[40:43]
	s_waitcnt lgkmcnt(5)
	v_mfma_f32_16x16x32_bf16 v[44:47], v[166:169], v[162:165], v[44:47]
	s_waitcnt lgkmcnt(4)
	v_mfma_f32_16x16x32_bf16 v[56:59], v[158:161], v[178:181], v[56:59]
	s_mov_b32 m0, s27
	v_mfma_f32_16x16x32_bf16 v[60:63], v[166:169], v[178:181], v[60:63]
	global_load_lds_dwordx4 v0, s[46:47]
	s_waitcnt lgkmcnt(3)
	v_mfma_f32_16x16x32_bf16 v[48:51], v[214:217], v[162:165], v[48:51]
	v_mfma_f32_16x16x32_bf16 v[64:67], v[214:217], v[178:181], v[64:67]
	s_waitcnt lgkmcnt(2)
	v_mfma_f32_16x16x32_bf16 v[174:177], v[218:221], v[162:165], v[174:177]
	ds_read_b128 v[162:165], v16
	v_mfma_f32_16x16x32_bf16 v[170:173], v[218:221], v[178:181], v[170:173]
	ds_read_b128 v[178:181], v17
	s_waitcnt lgkmcnt(3)
	s_mov_b32 m0, s28
	v_mfma_f32_16x16x32_bf16 v[72:75], v[158:161], v[222:225], v[72:75]
	global_load_lds_dwordx4 v0, s[48:49]
	v_mfma_f32_16x16x32_bf16 v[76:79], v[166:169], v[222:225], v[76:79]
	v_mfma_f32_16x16x32_bf16 v[80:83], v[214:217], v[222:225], v[80:83]
	v_mfma_f32_16x16x32_bf16 v[32:35], v[218:221], v[222:225], v[32:35]
	ds_read_b128 v[222:225], v18
	s_waitcnt lgkmcnt(3)
	v_mfma_f32_16x16x32_bf16 v[88:91], v[158:161], v[226:229], v[88:91]
	s_mov_b32 m0, s29
	v_mfma_f32_16x16x32_bf16 v[92:95], v[166:169], v[226:229], v[92:95]
	global_load_lds_dwordx4 v2, s[46:47]
	v_mfma_f32_16x16x32_bf16 v[96:99], v[214:217], v[226:229], v[96:99]
	v_mfma_f32_16x16x32_bf16 v[36:39], v[218:221], v[226:229], v[36:39]
	ds_read_b128 v[226:229], v19
	s_waitcnt lgkmcnt(3)
	v_mfma_f32_16x16x32_bf16 v[104:107], v[158:161], v[162:165], v[104:107]
	s_waitcnt lgkmcnt(2)
	v_mfma_f32_16x16x32_bf16 v[116:119], v[158:161], v[178:181], v[116:119]
	s_waitcnt lgkmcnt(1)
	s_mov_b32 m0, s30
	v_mfma_f32_16x16x32_bf16 v[128:131], v[158:161], v[222:225], v[128:131]
	global_load_lds_dwordx4 v2, s[48:49]
	s_waitcnt lgkmcnt(0)
	v_mfma_f32_16x16x32_bf16 v[100:103], v[158:161], v[226:229], v[100:103]
	ds_read_b128 v[158:161], v20
	v_mfma_f32_16x16x32_bf16 v[108:111], v[166:169], v[162:165], v[108:111]
	v_mfma_f32_16x16x32_bf16 v[120:123], v[166:169], v[178:181], v[120:123]
	v_mfma_f32_16x16x32_bf16 v[132:135], v[166:169], v[222:225], v[132:135]
	s_mov_b32 m0, s31
	v_mfma_f32_16x16x32_bf16 v[140:143], v[166:169], v[226:229], v[140:143]
	global_load_lds_dwordx4 v4, s[46:47]
	ds_read_b128 v[166:169], v24
	v_mfma_f32_16x16x32_bf16 v[112:115], v[214:217], v[162:165], v[112:115]
	v_mfma_f32_16x16x32_bf16 v[52:55], v[218:221], v[162:165], v[52:55]
	ds_read_b128 v[162:165], v21
	v_mfma_f32_16x16x32_bf16 v[124:127], v[214:217], v[178:181], v[124:127]
	v_mfma_f32_16x16x32_bf16 v[68:71], v[218:221], v[178:181], v[68:71]
	ds_read_b128 v[178:181], v25
	s_mov_b32 m0, s34
	v_mfma_f32_16x16x32_bf16 v[136:139], v[214:217], v[222:225], v[136:139]
	global_load_lds_dwordx4 v4, s[48:49]
	v_mfma_f32_16x16x32_bf16 v[84:87], v[218:221], v[222:225], v[84:87]
	ds_read_b128 v[222:225], v26
	v_mfma_f32_16x16x32_bf16 v[150:153], v[214:217], v[226:229], v[150:153]
	ds_read_b128 v[214:217], v23
	v_mfma_f32_16x16x32_bf16 v[154:157], v[218:221], v[226:229], v[154:157]
	ds_read_b128 v[218:221], v22
	ds_read_b128 v[226:229], v27
	s_waitcnt lgkmcnt(6)
	v_mfma_f32_16x16x32_bf16 v[40:43], v[158:161], v[166:169], v[40:43]
	s_waitcnt lgkmcnt(5)
	s_mov_b32 m0, s35
	v_mfma_f32_16x16x32_bf16 v[44:47], v[162:165], v[166:169], v[44:47]
	global_load_lds_dwordx4 v146, s[46:47]
	s_waitcnt lgkmcnt(4)
	v_mfma_f32_16x16x32_bf16 v[56:59], v[158:161], v[178:181], v[56:59]
	v_mfma_f32_16x16x32_bf16 v[60:63], v[162:165], v[178:181], v[60:63]
	s_waitcnt lgkmcnt(3)
	v_mfma_f32_16x16x32_bf16 v[72:75], v[158:161], v[222:225], v[72:75]
	v_mfma_f32_16x16x32_bf16 v[76:79], v[162:165], v[222:225], v[76:79]
	s_waitcnt lgkmcnt(2)
	s_mov_b32 m0, s36
	v_mfma_f32_16x16x32_bf16 v[48:51], v[214:217], v[166:169], v[48:51]
	global_load_lds_dwordx4 v146, s[48:49]
	s_waitcnt lgkmcnt(1)
	v_mfma_f32_16x16x32_bf16 v[174:177], v[218:221], v[166:169], v[174:177]
	ds_read_b128 v[166:169], v28
	v_mfma_f32_16x16x32_bf16 v[64:67], v[214:217], v[178:181], v[64:67]
	v_mfma_f32_16x16x32_bf16 v[170:173], v[218:221], v[178:181], v[170:173]
	ds_read_b128 v[178:181], v29
	v_mfma_f32_16x16x32_bf16 v[80:83], v[214:217], v[222:225], v[80:83]
	v_mfma_f32_16x16x32_bf16 v[32:35], v[218:221], v[222:225], v[32:35]
	ds_read_b128 v[222:225], v30
	s_waitcnt lgkmcnt(3)
	v_mfma_f32_16x16x32_bf16 v[88:91], v[158:161], v[226:229], v[88:91]
	v_mfma_f32_16x16x32_bf16 v[92:95], v[162:165], v[226:229], v[92:95]
	v_mfma_f32_16x16x32_bf16 v[96:99], v[214:217], v[226:229], v[96:99]
	v_mfma_f32_16x16x32_bf16 v[36:39], v[218:221], v[226:229], v[36:39]
	ds_read_b128 v[226:229], v31
	s_waitcnt lgkmcnt(3)
	v_mfma_f32_16x16x32_bf16 v[104:107], v[158:161], v[166:169], v[104:107]
	v_mfma_f32_16x16x32_bf16 v[108:111], v[162:165], v[166:169], v[108:111]
	v_mfma_f32_16x16x32_bf16 v[112:115], v[214:217], v[166:169], v[112:115]
	v_mfma_f32_16x16x32_bf16 v[52:55], v[218:221], v[166:169], v[52:55]
	s_waitcnt lgkmcnt(2)
	v_mfma_f32_16x16x32_bf16 v[116:119], v[158:161], v[178:181], v[116:119]
	v_mfma_f32_16x16x32_bf16 v[120:123], v[162:165], v[178:181], v[120:123]
	v_mfma_f32_16x16x32_bf16 v[124:127], v[214:217], v[178:181], v[124:127]
	v_mfma_f32_16x16x32_bf16 v[68:71], v[218:221], v[178:181], v[68:71]
	s_waitcnt lgkmcnt(1)
	v_mfma_f32_16x16x32_bf16 v[128:131], v[158:161], v[222:225], v[128:131]
	v_mfma_f32_16x16x32_bf16 v[132:135], v[162:165], v[222:225], v[132:135]
	v_mfma_f32_16x16x32_bf16 v[136:139], v[214:217], v[222:225], v[136:139]
	v_mfma_f32_16x16x32_bf16 v[84:87], v[218:221], v[222:225], v[84:87]
	s_waitcnt lgkmcnt(0)
	v_mfma_f32_16x16x32_bf16 v[100:103], v[158:161], v[226:229], v[100:103]
	v_mfma_f32_16x16x32_bf16 v[140:143], v[162:165], v[226:229], v[140:143]
	v_mfma_f32_16x16x32_bf16 v[150:153], v[214:217], v[226:229], v[150:153]
	v_mfma_f32_16x16x32_bf16 v[154:157], v[218:221], v[226:229], v[154:157]
	s_add_u32 s46, s0, 0x2180
	s_addc_u32 s47, s1, 0
	s_add_u32 s48, s14, 0x2180
	s_waitcnt vmcnt(0)
	s_barrier
	s_addc_u32 s49, s15, 0
	ds_read_b128 v[158:161], v7 offset:32768
	ds_read_b128 v[162:165], v6
	ds_read_b128 v[166:169], v7 offset:34816
	ds_read_b128 v[178:181], v6 offset:2048
	ds_read_b128 v[214:217], v7 offset:36864
	ds_read_b128 v[218:221], v7 offset:38912
	ds_read_b128 v[222:225], v6 offset:4096
	ds_read_b128 v[226:229], v6 offset:6144
	s_waitcnt lgkmcnt(6)
	v_mfma_f32_16x16x32_bf16 v[40:43], v[158:161], v[162:165], v[40:43]
	s_waitcnt lgkmcnt(5)
	v_mfma_f32_16x16x32_bf16 v[44:47], v[166:169], v[162:165], v[44:47]
	s_waitcnt lgkmcnt(4)
	v_mfma_f32_16x16x32_bf16 v[56:59], v[158:161], v[178:181], v[56:59]
	s_mov_b32 m0, s38
	v_mfma_f32_16x16x32_bf16 v[60:63], v[166:169], v[178:181], v[60:63]
	global_load_lds_dwordx4 v0, s[46:47]
	s_waitcnt lgkmcnt(3)
	v_mfma_f32_16x16x32_bf16 v[48:51], v[214:217], v[162:165], v[48:51]
	v_mfma_f32_16x16x32_bf16 v[64:67], v[214:217], v[178:181], v[64:67]
	s_waitcnt lgkmcnt(2)
	v_mfma_f32_16x16x32_bf16 v[174:177], v[218:221], v[162:165], v[174:177]
	ds_read_b128 v[162:165], v6 offset:8192
	v_mfma_f32_16x16x32_bf16 v[170:173], v[218:221], v[178:181], v[170:173]
	ds_read_b128 v[178:181], v6 offset:10240
	s_waitcnt lgkmcnt(3)
	s_mov_b32 m0, s37
	v_mfma_f32_16x16x32_bf16 v[72:75], v[158:161], v[222:225], v[72:75]
	global_load_lds_dwordx4 v0, s[48:49]
	v_mfma_f32_16x16x32_bf16 v[76:79], v[166:169], v[222:225], v[76:79]
	v_mfma_f32_16x16x32_bf16 v[80:83], v[214:217], v[222:225], v[80:83]
	v_mfma_f32_16x16x32_bf16 v[32:35], v[218:221], v[222:225], v[32:35]
	ds_read_b128 v[222:225], v6 offset:12288
	s_waitcnt lgkmcnt(3)
	v_mfma_f32_16x16x32_bf16 v[88:91], v[158:161], v[226:229], v[88:91]
	s_mov_b32 m0, s39
	v_mfma_f32_16x16x32_bf16 v[92:95], v[166:169], v[226:229], v[92:95]
	global_load_lds_dwordx4 v2, s[46:47]
	v_mfma_f32_16x16x32_bf16 v[96:99], v[214:217], v[226:229], v[96:99]
	v_mfma_f32_16x16x32_bf16 v[36:39], v[218:221], v[226:229], v[36:39]
	ds_read_b128 v[226:229], v6 offset:14336
	s_waitcnt lgkmcnt(3)
	v_mfma_f32_16x16x32_bf16 v[104:107], v[158:161], v[162:165], v[104:107]
	s_waitcnt lgkmcnt(2)
	v_mfma_f32_16x16x32_bf16 v[116:119], v[158:161], v[178:181], v[116:119]
	s_waitcnt lgkmcnt(1)
	s_mov_b32 m0, s40
	v_mfma_f32_16x16x32_bf16 v[128:131], v[158:161], v[222:225], v[128:131]
	global_load_lds_dwordx4 v2, s[48:49]
	s_waitcnt lgkmcnt(0)
	v_mfma_f32_16x16x32_bf16 v[100:103], v[158:161], v[226:229], v[100:103]
	ds_read_b128 v[158:161], v7 offset:33792
	v_mfma_f32_16x16x32_bf16 v[108:111], v[166:169], v[162:165], v[108:111]
	v_mfma_f32_16x16x32_bf16 v[120:123], v[166:169], v[178:181], v[120:123]
	v_mfma_f32_16x16x32_bf16 v[132:135], v[166:169], v[222:225], v[132:135]
	s_mov_b32 m0, s41
	v_mfma_f32_16x16x32_bf16 v[140:143], v[166:169], v[226:229], v[140:143]
	global_load_lds_dwordx4 v4, s[46:47]
	ds_read_b128 v[166:169], v6 offset:1024
	v_mfma_f32_16x16x32_bf16 v[112:115], v[214:217], v[162:165], v[112:115]
	v_mfma_f32_16x16x32_bf16 v[52:55], v[218:221], v[162:165], v[52:55]
	ds_read_b128 v[162:165], v7 offset:35840
	v_mfma_f32_16x16x32_bf16 v[124:127], v[214:217], v[178:181], v[124:127]
	v_mfma_f32_16x16x32_bf16 v[68:71], v[218:221], v[178:181], v[68:71]
	ds_read_b128 v[178:181], v6 offset:3072
	s_mov_b32 m0, s42
	v_mfma_f32_16x16x32_bf16 v[136:139], v[214:217], v[222:225], v[136:139]
	global_load_lds_dwordx4 v4, s[48:49]
	v_mfma_f32_16x16x32_bf16 v[84:87], v[218:221], v[222:225], v[84:87]
	ds_read_b128 v[222:225], v6 offset:5120
	v_mfma_f32_16x16x32_bf16 v[150:153], v[214:217], v[226:229], v[150:153]
	ds_read_b128 v[214:217], v7 offset:37888
	v_mfma_f32_16x16x32_bf16 v[154:157], v[218:221], v[226:229], v[154:157]
	ds_read_b128 v[218:221], v7 offset:39936
	ds_read_b128 v[226:229], v6 offset:7168
	s_waitcnt lgkmcnt(6)
	v_mfma_f32_16x16x32_bf16 v[40:43], v[158:161], v[166:169], v[40:43]
	s_waitcnt lgkmcnt(5)
	s_mov_b32 m0, s43
	v_mfma_f32_16x16x32_bf16 v[44:47], v[162:165], v[166:169], v[44:47]
	global_load_lds_dwordx4 v146, s[46:47]
	s_waitcnt lgkmcnt(4)
	v_mfma_f32_16x16x32_bf16 v[56:59], v[158:161], v[178:181], v[56:59]
	v_mfma_f32_16x16x32_bf16 v[60:63], v[162:165], v[178:181], v[60:63]
	s_waitcnt lgkmcnt(3)
	v_mfma_f32_16x16x32_bf16 v[72:75], v[158:161], v[222:225], v[72:75]
	v_mfma_f32_16x16x32_bf16 v[76:79], v[162:165], v[222:225], v[76:79]
	s_waitcnt lgkmcnt(2)
	s_mov_b32 m0, s44
	v_mfma_f32_16x16x32_bf16 v[48:51], v[214:217], v[166:169], v[48:51]
	global_load_lds_dwordx4 v146, s[48:49]
	s_waitcnt lgkmcnt(1)
	v_mfma_f32_16x16x32_bf16 v[174:177], v[218:221], v[166:169], v[174:177]
	ds_read_b128 v[166:169], v6 offset:9216
	v_mfma_f32_16x16x32_bf16 v[64:67], v[214:217], v[178:181], v[64:67]
	v_mfma_f32_16x16x32_bf16 v[170:173], v[218:221], v[178:181], v[170:173]
	ds_read_b128 v[178:181], v6 offset:11264
	v_mfma_f32_16x16x32_bf16 v[80:83], v[214:217], v[222:225], v[80:83]
	v_mfma_f32_16x16x32_bf16 v[32:35], v[218:221], v[222:225], v[32:35]
	ds_read_b128 v[222:225], v6 offset:13312
	s_waitcnt lgkmcnt(3)
	v_mfma_f32_16x16x32_bf16 v[88:91], v[158:161], v[226:229], v[88:91]
	v_mfma_f32_16x16x32_bf16 v[92:95], v[162:165], v[226:229], v[92:95]
	v_mfma_f32_16x16x32_bf16 v[96:99], v[214:217], v[226:229], v[96:99]
	v_mfma_f32_16x16x32_bf16 v[36:39], v[218:221], v[226:229], v[36:39]
	ds_read_b128 v[226:229], v6 offset:15360
	s_waitcnt lgkmcnt(3)
	v_mfma_f32_16x16x32_bf16 v[104:107], v[158:161], v[166:169], v[104:107]
	v_mfma_f32_16x16x32_bf16 v[108:111], v[162:165], v[166:169], v[108:111]
	v_mfma_f32_16x16x32_bf16 v[112:115], v[214:217], v[166:169], v[112:115]
	v_mfma_f32_16x16x32_bf16 v[52:55], v[218:221], v[166:169], v[52:55]
	s_waitcnt lgkmcnt(2)
	v_mfma_f32_16x16x32_bf16 v[116:119], v[158:161], v[178:181], v[116:119]
	v_mfma_f32_16x16x32_bf16 v[120:123], v[162:165], v[178:181], v[120:123]
	v_mfma_f32_16x16x32_bf16 v[124:127], v[214:217], v[178:181], v[124:127]
	v_mfma_f32_16x16x32_bf16 v[68:71], v[218:221], v[178:181], v[68:71]
	s_waitcnt lgkmcnt(1)
	v_mfma_f32_16x16x32_bf16 v[128:131], v[158:161], v[222:225], v[128:131]
	v_mfma_f32_16x16x32_bf16 v[132:135], v[162:165], v[222:225], v[132:135]
	v_mfma_f32_16x16x32_bf16 v[136:139], v[214:217], v[222:225], v[136:139]
	v_mfma_f32_16x16x32_bf16 v[84:87], v[218:221], v[222:225], v[84:87]
	s_waitcnt lgkmcnt(0)
	v_mfma_f32_16x16x32_bf16 v[100:103], v[158:161], v[226:229], v[100:103]
	v_mfma_f32_16x16x32_bf16 v[140:143], v[162:165], v[226:229], v[140:143]
	v_mfma_f32_16x16x32_bf16 v[150:153], v[214:217], v[226:229], v[150:153]
	v_mfma_f32_16x16x32_bf16 v[154:157], v[218:221], v[226:229], v[154:157]
	s_add_u32 s46, s0, 0x2200
	s_addc_u32 s47, s1, 0
	s_add_u32 s48, s14, 0x2200
	s_waitcnt vmcnt(0)
	s_barrier
	s_addc_u32 s49, s15, 0
	ds_read_b128 v[158:161], v8
	ds_read_b128 v[162:165], v12
	ds_read_b128 v[166:169], v9
	ds_read_b128 v[178:181], v13
	ds_read_b128 v[214:217], v11
	ds_read_b128 v[218:221], v10
	ds_read_b128 v[222:225], v14
	ds_read_b128 v[226:229], v15
	s_waitcnt lgkmcnt(6)
	v_mfma_f32_16x16x32_bf16 v[40:43], v[158:161], v[162:165], v[40:43]
	s_waitcnt lgkmcnt(5)
	v_mfma_f32_16x16x32_bf16 v[44:47], v[166:169], v[162:165], v[44:47]
	s_waitcnt lgkmcnt(4)
	v_mfma_f32_16x16x32_bf16 v[56:59], v[158:161], v[178:181], v[56:59]
	s_mov_b32 m0, s27
	v_mfma_f32_16x16x32_bf16 v[60:63], v[166:169], v[178:181], v[60:63]
	global_load_lds_dwordx4 v0, s[46:47]
	s_waitcnt lgkmcnt(3)
	v_mfma_f32_16x16x32_bf16 v[48:51], v[214:217], v[162:165], v[48:51]
	v_mfma_f32_16x16x32_bf16 v[64:67], v[214:217], v[178:181], v[64:67]
	s_waitcnt lgkmcnt(2)
	v_mfma_f32_16x16x32_bf16 v[174:177], v[218:221], v[162:165], v[174:177]
	ds_read_b128 v[162:165], v16
	v_mfma_f32_16x16x32_bf16 v[170:173], v[218:221], v[178:181], v[170:173]
	ds_read_b128 v[178:181], v17
	s_waitcnt lgkmcnt(3)
	s_mov_b32 m0, s28
	v_mfma_f32_16x16x32_bf16 v[72:75], v[158:161], v[222:225], v[72:75]
	global_load_lds_dwordx4 v0, s[48:49]
	v_mfma_f32_16x16x32_bf16 v[76:79], v[166:169], v[222:225], v[76:79]
	v_mfma_f32_16x16x32_bf16 v[80:83], v[214:217], v[222:225], v[80:83]
	v_mfma_f32_16x16x32_bf16 v[32:35], v[218:221], v[222:225], v[32:35]
	ds_read_b128 v[222:225], v18
	s_waitcnt lgkmcnt(3)
	v_mfma_f32_16x16x32_bf16 v[88:91], v[158:161], v[226:229], v[88:91]
	s_mov_b32 m0, s29
	v_mfma_f32_16x16x32_bf16 v[92:95], v[166:169], v[226:229], v[92:95]
	global_load_lds_dwordx4 v2, s[46:47]
	v_mfma_f32_16x16x32_bf16 v[96:99], v[214:217], v[226:229], v[96:99]
	v_mfma_f32_16x16x32_bf16 v[36:39], v[218:221], v[226:229], v[36:39]
	ds_read_b128 v[226:229], v19
	s_waitcnt lgkmcnt(3)
	v_mfma_f32_16x16x32_bf16 v[104:107], v[158:161], v[162:165], v[104:107]
	s_waitcnt lgkmcnt(2)
	v_mfma_f32_16x16x32_bf16 v[116:119], v[158:161], v[178:181], v[116:119]
	s_waitcnt lgkmcnt(1)
	s_mov_b32 m0, s30
	v_mfma_f32_16x16x32_bf16 v[128:131], v[158:161], v[222:225], v[128:131]
	global_load_lds_dwordx4 v2, s[48:49]
	s_waitcnt lgkmcnt(0)
	v_mfma_f32_16x16x32_bf16 v[100:103], v[158:161], v[226:229], v[100:103]
	ds_read_b128 v[158:161], v20
	v_mfma_f32_16x16x32_bf16 v[108:111], v[166:169], v[162:165], v[108:111]
	v_mfma_f32_16x16x32_bf16 v[120:123], v[166:169], v[178:181], v[120:123]
	v_mfma_f32_16x16x32_bf16 v[132:135], v[166:169], v[222:225], v[132:135]
	s_mov_b32 m0, s31
	v_mfma_f32_16x16x32_bf16 v[140:143], v[166:169], v[226:229], v[140:143]
	global_load_lds_dwordx4 v4, s[46:47]
	ds_read_b128 v[166:169], v24
	v_mfma_f32_16x16x32_bf16 v[112:115], v[214:217], v[162:165], v[112:115]
	v_mfma_f32_16x16x32_bf16 v[52:55], v[218:221], v[162:165], v[52:55]
	ds_read_b128 v[162:165], v21
	v_mfma_f32_16x16x32_bf16 v[124:127], v[214:217], v[178:181], v[124:127]
	v_mfma_f32_16x16x32_bf16 v[68:71], v[218:221], v[178:181], v[68:71]
	ds_read_b128 v[178:181], v25
	s_mov_b32 m0, s34
	v_mfma_f32_16x16x32_bf16 v[136:139], v[214:217], v[222:225], v[136:139]
	global_load_lds_dwordx4 v4, s[48:49]
	v_mfma_f32_16x16x32_bf16 v[84:87], v[218:221], v[222:225], v[84:87]
	ds_read_b128 v[222:225], v26
	v_mfma_f32_16x16x32_bf16 v[150:153], v[214:217], v[226:229], v[150:153]
	ds_read_b128 v[214:217], v23
	v_mfma_f32_16x16x32_bf16 v[154:157], v[218:221], v[226:229], v[154:157]
	ds_read_b128 v[218:221], v22
	ds_read_b128 v[226:229], v27
	s_waitcnt lgkmcnt(6)
	v_mfma_f32_16x16x32_bf16 v[40:43], v[158:161], v[166:169], v[40:43]
	s_waitcnt lgkmcnt(5)
	s_mov_b32 m0, s35
	v_mfma_f32_16x16x32_bf16 v[44:47], v[162:165], v[166:169], v[44:47]
	global_load_lds_dwordx4 v146, s[46:47]
	s_waitcnt lgkmcnt(4)
	v_mfma_f32_16x16x32_bf16 v[56:59], v[158:161], v[178:181], v[56:59]
	v_mfma_f32_16x16x32_bf16 v[60:63], v[162:165], v[178:181], v[60:63]
	s_waitcnt lgkmcnt(3)
	v_mfma_f32_16x16x32_bf16 v[72:75], v[158:161], v[222:225], v[72:75]
	v_mfma_f32_16x16x32_bf16 v[76:79], v[162:165], v[222:225], v[76:79]
	s_waitcnt lgkmcnt(2)
	s_mov_b32 m0, s36
	v_mfma_f32_16x16x32_bf16 v[48:51], v[214:217], v[166:169], v[48:51]
	global_load_lds_dwordx4 v146, s[48:49]
	s_waitcnt lgkmcnt(1)
	v_mfma_f32_16x16x32_bf16 v[174:177], v[218:221], v[166:169], v[174:177]
	ds_read_b128 v[166:169], v28
	v_mfma_f32_16x16x32_bf16 v[64:67], v[214:217], v[178:181], v[64:67]
	v_mfma_f32_16x16x32_bf16 v[170:173], v[218:221], v[178:181], v[170:173]
	ds_read_b128 v[178:181], v29
	v_mfma_f32_16x16x32_bf16 v[80:83], v[214:217], v[222:225], v[80:83]
	v_mfma_f32_16x16x32_bf16 v[32:35], v[218:221], v[222:225], v[32:35]
	ds_read_b128 v[222:225], v30
	s_waitcnt lgkmcnt(3)
	v_mfma_f32_16x16x32_bf16 v[88:91], v[158:161], v[226:229], v[88:91]
	v_mfma_f32_16x16x32_bf16 v[92:95], v[162:165], v[226:229], v[92:95]
	v_mfma_f32_16x16x32_bf16 v[96:99], v[214:217], v[226:229], v[96:99]
	v_mfma_f32_16x16x32_bf16 v[36:39], v[218:221], v[226:229], v[36:39]
	ds_read_b128 v[226:229], v31
	s_waitcnt lgkmcnt(3)
	v_mfma_f32_16x16x32_bf16 v[104:107], v[158:161], v[166:169], v[104:107]
	v_mfma_f32_16x16x32_bf16 v[108:111], v[162:165], v[166:169], v[108:111]
	v_mfma_f32_16x16x32_bf16 v[112:115], v[214:217], v[166:169], v[112:115]
	v_mfma_f32_16x16x32_bf16 v[52:55], v[218:221], v[166:169], v[52:55]
	s_waitcnt lgkmcnt(2)
	v_mfma_f32_16x16x32_bf16 v[116:119], v[158:161], v[178:181], v[116:119]
	v_mfma_f32_16x16x32_bf16 v[120:123], v[162:165], v[178:181], v[120:123]
	v_mfma_f32_16x16x32_bf16 v[124:127], v[214:217], v[178:181], v[124:127]
	v_mfma_f32_16x16x32_bf16 v[68:71], v[218:221], v[178:181], v[68:71]
	s_waitcnt lgkmcnt(1)
	v_mfma_f32_16x16x32_bf16 v[128:131], v[158:161], v[222:225], v[128:131]
	v_mfma_f32_16x16x32_bf16 v[132:135], v[162:165], v[222:225], v[132:135]
	v_mfma_f32_16x16x32_bf16 v[136:139], v[214:217], v[222:225], v[136:139]
	v_mfma_f32_16x16x32_bf16 v[84:87], v[218:221], v[222:225], v[84:87]
	s_waitcnt lgkmcnt(0)
	v_mfma_f32_16x16x32_bf16 v[100:103], v[158:161], v[226:229], v[100:103]
	v_mfma_f32_16x16x32_bf16 v[140:143], v[162:165], v[226:229], v[140:143]
	v_mfma_f32_16x16x32_bf16 v[150:153], v[214:217], v[226:229], v[150:153]
	v_mfma_f32_16x16x32_bf16 v[154:157], v[218:221], v[226:229], v[154:157]
	s_add_u32 s46, s0, 0x2280
	s_addc_u32 s47, s1, 0
	s_add_u32 s48, s14, 0x2280
	s_waitcnt vmcnt(0)
	s_barrier
	s_addc_u32 s49, s15, 0
	ds_read_b128 v[158:161], v7 offset:32768
	ds_read_b128 v[162:165], v6
	ds_read_b128 v[166:169], v7 offset:34816
	ds_read_b128 v[178:181], v6 offset:2048
	ds_read_b128 v[214:217], v7 offset:36864
	ds_read_b128 v[218:221], v7 offset:38912
	ds_read_b128 v[222:225], v6 offset:4096
	ds_read_b128 v[226:229], v6 offset:6144
	s_waitcnt lgkmcnt(6)
	v_mfma_f32_16x16x32_bf16 v[40:43], v[158:161], v[162:165], v[40:43]
	s_waitcnt lgkmcnt(5)
	v_mfma_f32_16x16x32_bf16 v[44:47], v[166:169], v[162:165], v[44:47]
	s_waitcnt lgkmcnt(4)
	v_mfma_f32_16x16x32_bf16 v[56:59], v[158:161], v[178:181], v[56:59]
	s_mov_b32 m0, s38
	v_mfma_f32_16x16x32_bf16 v[60:63], v[166:169], v[178:181], v[60:63]
	global_load_lds_dwordx4 v0, s[46:47]
	s_waitcnt lgkmcnt(3)
	v_mfma_f32_16x16x32_bf16 v[48:51], v[214:217], v[162:165], v[48:51]
	v_mfma_f32_16x16x32_bf16 v[64:67], v[214:217], v[178:181], v[64:67]
	s_waitcnt lgkmcnt(2)
	v_mfma_f32_16x16x32_bf16 v[174:177], v[218:221], v[162:165], v[174:177]
	ds_read_b128 v[162:165], v6 offset:8192
	v_mfma_f32_16x16x32_bf16 v[170:173], v[218:221], v[178:181], v[170:173]
	ds_read_b128 v[178:181], v6 offset:10240
	s_waitcnt lgkmcnt(3)
	s_mov_b32 m0, s37
	v_mfma_f32_16x16x32_bf16 v[72:75], v[158:161], v[222:225], v[72:75]
	global_load_lds_dwordx4 v0, s[48:49]
	v_mfma_f32_16x16x32_bf16 v[76:79], v[166:169], v[222:225], v[76:79]
	v_mfma_f32_16x16x32_bf16 v[80:83], v[214:217], v[222:225], v[80:83]
	v_mfma_f32_16x16x32_bf16 v[32:35], v[218:221], v[222:225], v[32:35]
	ds_read_b128 v[222:225], v6 offset:12288
	s_waitcnt lgkmcnt(3)
	v_mfma_f32_16x16x32_bf16 v[88:91], v[158:161], v[226:229], v[88:91]
	s_mov_b32 m0, s39
	v_mfma_f32_16x16x32_bf16 v[92:95], v[166:169], v[226:229], v[92:95]
	global_load_lds_dwordx4 v2, s[46:47]
	v_mfma_f32_16x16x32_bf16 v[96:99], v[214:217], v[226:229], v[96:99]
	v_mfma_f32_16x16x32_bf16 v[36:39], v[218:221], v[226:229], v[36:39]
	ds_read_b128 v[226:229], v6 offset:14336
	s_waitcnt lgkmcnt(3)
	v_mfma_f32_16x16x32_bf16 v[104:107], v[158:161], v[162:165], v[104:107]
	s_waitcnt lgkmcnt(2)
	v_mfma_f32_16x16x32_bf16 v[116:119], v[158:161], v[178:181], v[116:119]
	s_waitcnt lgkmcnt(1)
	s_mov_b32 m0, s40
	v_mfma_f32_16x16x32_bf16 v[128:131], v[158:161], v[222:225], v[128:131]
	global_load_lds_dwordx4 v2, s[48:49]
	s_waitcnt lgkmcnt(0)
	v_mfma_f32_16x16x32_bf16 v[100:103], v[158:161], v[226:229], v[100:103]
	ds_read_b128 v[158:161], v7 offset:33792
	v_mfma_f32_16x16x32_bf16 v[108:111], v[166:169], v[162:165], v[108:111]
	v_mfma_f32_16x16x32_bf16 v[120:123], v[166:169], v[178:181], v[120:123]
	v_mfma_f32_16x16x32_bf16 v[132:135], v[166:169], v[222:225], v[132:135]
	s_mov_b32 m0, s41
	v_mfma_f32_16x16x32_bf16 v[140:143], v[166:169], v[226:229], v[140:143]
	global_load_lds_dwordx4 v4, s[46:47]
	ds_read_b128 v[166:169], v6 offset:1024
	v_mfma_f32_16x16x32_bf16 v[112:115], v[214:217], v[162:165], v[112:115]
	v_mfma_f32_16x16x32_bf16 v[52:55], v[218:221], v[162:165], v[52:55]
	ds_read_b128 v[162:165], v7 offset:35840
	v_mfma_f32_16x16x32_bf16 v[124:127], v[214:217], v[178:181], v[124:127]
	v_mfma_f32_16x16x32_bf16 v[68:71], v[218:221], v[178:181], v[68:71]
	ds_read_b128 v[178:181], v6 offset:3072
	s_mov_b32 m0, s42
	v_mfma_f32_16x16x32_bf16 v[136:139], v[214:217], v[222:225], v[136:139]
	global_load_lds_dwordx4 v4, s[48:49]
	v_mfma_f32_16x16x32_bf16 v[84:87], v[218:221], v[222:225], v[84:87]
	ds_read_b128 v[222:225], v6 offset:5120
	v_mfma_f32_16x16x32_bf16 v[150:153], v[214:217], v[226:229], v[150:153]
	ds_read_b128 v[214:217], v7 offset:37888
	v_mfma_f32_16x16x32_bf16 v[154:157], v[218:221], v[226:229], v[154:157]
	ds_read_b128 v[218:221], v7 offset:39936
	ds_read_b128 v[226:229], v6 offset:7168
	s_waitcnt lgkmcnt(6)
	v_mfma_f32_16x16x32_bf16 v[40:43], v[158:161], v[166:169], v[40:43]
	s_waitcnt lgkmcnt(5)
	s_mov_b32 m0, s43
	v_mfma_f32_16x16x32_bf16 v[44:47], v[162:165], v[166:169], v[44:47]
	global_load_lds_dwordx4 v146, s[46:47]
	s_waitcnt lgkmcnt(4)
	v_mfma_f32_16x16x32_bf16 v[56:59], v[158:161], v[178:181], v[56:59]
	v_mfma_f32_16x16x32_bf16 v[60:63], v[162:165], v[178:181], v[60:63]
	s_waitcnt lgkmcnt(3)
	v_mfma_f32_16x16x32_bf16 v[72:75], v[158:161], v[222:225], v[72:75]
	v_mfma_f32_16x16x32_bf16 v[76:79], v[162:165], v[222:225], v[76:79]
	s_waitcnt lgkmcnt(2)
	s_mov_b32 m0, s44
	v_mfma_f32_16x16x32_bf16 v[48:51], v[214:217], v[166:169], v[48:51]
	global_load_lds_dwordx4 v146, s[48:49]
	s_waitcnt lgkmcnt(1)
	v_mfma_f32_16x16x32_bf16 v[174:177], v[218:221], v[166:169], v[174:177]
	ds_read_b128 v[166:169], v6 offset:9216
	v_mfma_f32_16x16x32_bf16 v[64:67], v[214:217], v[178:181], v[64:67]
	v_mfma_f32_16x16x32_bf16 v[170:173], v[218:221], v[178:181], v[170:173]
	ds_read_b128 v[178:181], v6 offset:11264
	v_mfma_f32_16x16x32_bf16 v[80:83], v[214:217], v[222:225], v[80:83]
	v_mfma_f32_16x16x32_bf16 v[32:35], v[218:221], v[222:225], v[32:35]
	ds_read_b128 v[222:225], v6 offset:13312
	s_waitcnt lgkmcnt(3)
	v_mfma_f32_16x16x32_bf16 v[88:91], v[158:161], v[226:229], v[88:91]
	v_mfma_f32_16x16x32_bf16 v[92:95], v[162:165], v[226:229], v[92:95]
	v_mfma_f32_16x16x32_bf16 v[96:99], v[214:217], v[226:229], v[96:99]
	v_mfma_f32_16x16x32_bf16 v[36:39], v[218:221], v[226:229], v[36:39]
	ds_read_b128 v[226:229], v6 offset:15360
	s_waitcnt lgkmcnt(3)
	v_mfma_f32_16x16x32_bf16 v[104:107], v[158:161], v[166:169], v[104:107]
	v_mfma_f32_16x16x32_bf16 v[108:111], v[162:165], v[166:169], v[108:111]
	v_mfma_f32_16x16x32_bf16 v[112:115], v[214:217], v[166:169], v[112:115]
	v_mfma_f32_16x16x32_bf16 v[52:55], v[218:221], v[166:169], v[52:55]
	s_waitcnt lgkmcnt(2)
	v_mfma_f32_16x16x32_bf16 v[116:119], v[158:161], v[178:181], v[116:119]
	v_mfma_f32_16x16x32_bf16 v[120:123], v[162:165], v[178:181], v[120:123]
	v_mfma_f32_16x16x32_bf16 v[124:127], v[214:217], v[178:181], v[124:127]
	v_mfma_f32_16x16x32_bf16 v[68:71], v[218:221], v[178:181], v[68:71]
	s_waitcnt lgkmcnt(1)
	v_mfma_f32_16x16x32_bf16 v[128:131], v[158:161], v[222:225], v[128:131]
	v_mfma_f32_16x16x32_bf16 v[132:135], v[162:165], v[222:225], v[132:135]
	v_mfma_f32_16x16x32_bf16 v[136:139], v[214:217], v[222:225], v[136:139]
	v_mfma_f32_16x16x32_bf16 v[84:87], v[218:221], v[222:225], v[84:87]
	s_waitcnt lgkmcnt(0)
	v_mfma_f32_16x16x32_bf16 v[100:103], v[158:161], v[226:229], v[100:103]
	v_mfma_f32_16x16x32_bf16 v[140:143], v[162:165], v[226:229], v[140:143]
	v_mfma_f32_16x16x32_bf16 v[150:153], v[214:217], v[226:229], v[150:153]
	v_mfma_f32_16x16x32_bf16 v[154:157], v[218:221], v[226:229], v[154:157]
	s_add_u32 s46, s0, 0x2300
	s_addc_u32 s47, s1, 0
	s_add_u32 s48, s14, 0x2300
	s_waitcnt vmcnt(0)
	s_barrier
	s_addc_u32 s49, s15, 0
	ds_read_b128 v[158:161], v8
	ds_read_b128 v[162:165], v12
	ds_read_b128 v[166:169], v9
	ds_read_b128 v[178:181], v13
	ds_read_b128 v[214:217], v11
	ds_read_b128 v[218:221], v10
	ds_read_b128 v[222:225], v14
	ds_read_b128 v[226:229], v15
	s_waitcnt lgkmcnt(6)
	v_mfma_f32_16x16x32_bf16 v[40:43], v[158:161], v[162:165], v[40:43]
	s_waitcnt lgkmcnt(5)
	v_mfma_f32_16x16x32_bf16 v[44:47], v[166:169], v[162:165], v[44:47]
	s_waitcnt lgkmcnt(4)
	v_mfma_f32_16x16x32_bf16 v[56:59], v[158:161], v[178:181], v[56:59]
	s_mov_b32 m0, s27
	v_mfma_f32_16x16x32_bf16 v[60:63], v[166:169], v[178:181], v[60:63]
	global_load_lds_dwordx4 v0, s[46:47]
	s_waitcnt lgkmcnt(3)
	v_mfma_f32_16x16x32_bf16 v[48:51], v[214:217], v[162:165], v[48:51]
	v_mfma_f32_16x16x32_bf16 v[64:67], v[214:217], v[178:181], v[64:67]
	s_waitcnt lgkmcnt(2)
	v_mfma_f32_16x16x32_bf16 v[174:177], v[218:221], v[162:165], v[174:177]
	ds_read_b128 v[162:165], v16
	v_mfma_f32_16x16x32_bf16 v[170:173], v[218:221], v[178:181], v[170:173]
	ds_read_b128 v[178:181], v17
	s_waitcnt lgkmcnt(3)
	s_mov_b32 m0, s28
	v_mfma_f32_16x16x32_bf16 v[72:75], v[158:161], v[222:225], v[72:75]
	global_load_lds_dwordx4 v0, s[48:49]
	v_mfma_f32_16x16x32_bf16 v[76:79], v[166:169], v[222:225], v[76:79]
	v_mfma_f32_16x16x32_bf16 v[80:83], v[214:217], v[222:225], v[80:83]
	v_mfma_f32_16x16x32_bf16 v[32:35], v[218:221], v[222:225], v[32:35]
	ds_read_b128 v[222:225], v18
	s_waitcnt lgkmcnt(3)
	v_mfma_f32_16x16x32_bf16 v[88:91], v[158:161], v[226:229], v[88:91]
	s_mov_b32 m0, s29
	v_mfma_f32_16x16x32_bf16 v[92:95], v[166:169], v[226:229], v[92:95]
	global_load_lds_dwordx4 v2, s[46:47]
	v_mfma_f32_16x16x32_bf16 v[96:99], v[214:217], v[226:229], v[96:99]
	v_mfma_f32_16x16x32_bf16 v[36:39], v[218:221], v[226:229], v[36:39]
	ds_read_b128 v[226:229], v19
	s_waitcnt lgkmcnt(3)
	v_mfma_f32_16x16x32_bf16 v[104:107], v[158:161], v[162:165], v[104:107]
	s_waitcnt lgkmcnt(2)
	v_mfma_f32_16x16x32_bf16 v[116:119], v[158:161], v[178:181], v[116:119]
	s_waitcnt lgkmcnt(1)
	s_mov_b32 m0, s30
	v_mfma_f32_16x16x32_bf16 v[128:131], v[158:161], v[222:225], v[128:131]
	global_load_lds_dwordx4 v2, s[48:49]
	s_waitcnt lgkmcnt(0)
	v_mfma_f32_16x16x32_bf16 v[100:103], v[158:161], v[226:229], v[100:103]
	ds_read_b128 v[158:161], v20
	v_mfma_f32_16x16x32_bf16 v[108:111], v[166:169], v[162:165], v[108:111]
	v_mfma_f32_16x16x32_bf16 v[120:123], v[166:169], v[178:181], v[120:123]
	v_mfma_f32_16x16x32_bf16 v[132:135], v[166:169], v[222:225], v[132:135]
	s_mov_b32 m0, s31
	v_mfma_f32_16x16x32_bf16 v[140:143], v[166:169], v[226:229], v[140:143]
	global_load_lds_dwordx4 v4, s[46:47]
	ds_read_b128 v[166:169], v24
	v_mfma_f32_16x16x32_bf16 v[112:115], v[214:217], v[162:165], v[112:115]
	v_mfma_f32_16x16x32_bf16 v[52:55], v[218:221], v[162:165], v[52:55]
	ds_read_b128 v[162:165], v21
	v_mfma_f32_16x16x32_bf16 v[124:127], v[214:217], v[178:181], v[124:127]
	v_mfma_f32_16x16x32_bf16 v[68:71], v[218:221], v[178:181], v[68:71]
	ds_read_b128 v[178:181], v25
	s_mov_b32 m0, s34
	v_mfma_f32_16x16x32_bf16 v[136:139], v[214:217], v[222:225], v[136:139]
	global_load_lds_dwordx4 v4, s[48:49]
	v_mfma_f32_16x16x32_bf16 v[84:87], v[218:221], v[222:225], v[84:87]
	ds_read_b128 v[222:225], v26
	v_mfma_f32_16x16x32_bf16 v[150:153], v[214:217], v[226:229], v[150:153]
	ds_read_b128 v[214:217], v23
	v_mfma_f32_16x16x32_bf16 v[154:157], v[218:221], v[226:229], v[154:157]
	ds_read_b128 v[218:221], v22
	ds_read_b128 v[226:229], v27
	s_waitcnt lgkmcnt(6)
	v_mfma_f32_16x16x32_bf16 v[40:43], v[158:161], v[166:169], v[40:43]
	s_waitcnt lgkmcnt(5)
	s_mov_b32 m0, s35
	v_mfma_f32_16x16x32_bf16 v[44:47], v[162:165], v[166:169], v[44:47]
	global_load_lds_dwordx4 v146, s[46:47]
	s_waitcnt lgkmcnt(4)
	v_mfma_f32_16x16x32_bf16 v[56:59], v[158:161], v[178:181], v[56:59]
	v_mfma_f32_16x16x32_bf16 v[60:63], v[162:165], v[178:181], v[60:63]
	s_waitcnt lgkmcnt(3)
	v_mfma_f32_16x16x32_bf16 v[72:75], v[158:161], v[222:225], v[72:75]
	v_mfma_f32_16x16x32_bf16 v[76:79], v[162:165], v[222:225], v[76:79]
	s_waitcnt lgkmcnt(2)
	s_mov_b32 m0, s36
	v_mfma_f32_16x16x32_bf16 v[48:51], v[214:217], v[166:169], v[48:51]
	global_load_lds_dwordx4 v146, s[48:49]
	s_waitcnt lgkmcnt(1)
	v_mfma_f32_16x16x32_bf16 v[174:177], v[218:221], v[166:169], v[174:177]
	ds_read_b128 v[166:169], v28
	v_mfma_f32_16x16x32_bf16 v[64:67], v[214:217], v[178:181], v[64:67]
	v_mfma_f32_16x16x32_bf16 v[170:173], v[218:221], v[178:181], v[170:173]
	ds_read_b128 v[178:181], v29
	v_mfma_f32_16x16x32_bf16 v[80:83], v[214:217], v[222:225], v[80:83]
	v_mfma_f32_16x16x32_bf16 v[32:35], v[218:221], v[222:225], v[32:35]
	ds_read_b128 v[222:225], v30
	s_waitcnt lgkmcnt(3)
	v_mfma_f32_16x16x32_bf16 v[88:91], v[158:161], v[226:229], v[88:91]
	v_mfma_f32_16x16x32_bf16 v[92:95], v[162:165], v[226:229], v[92:95]
	v_mfma_f32_16x16x32_bf16 v[96:99], v[214:217], v[226:229], v[96:99]
	v_mfma_f32_16x16x32_bf16 v[36:39], v[218:221], v[226:229], v[36:39]
	ds_read_b128 v[226:229], v31
	s_waitcnt lgkmcnt(3)
	v_mfma_f32_16x16x32_bf16 v[104:107], v[158:161], v[166:169], v[104:107]
	v_mfma_f32_16x16x32_bf16 v[108:111], v[162:165], v[166:169], v[108:111]
	v_mfma_f32_16x16x32_bf16 v[112:115], v[214:217], v[166:169], v[112:115]
	v_mfma_f32_16x16x32_bf16 v[52:55], v[218:221], v[166:169], v[52:55]
	s_waitcnt lgkmcnt(2)
	v_mfma_f32_16x16x32_bf16 v[116:119], v[158:161], v[178:181], v[116:119]
	v_mfma_f32_16x16x32_bf16 v[120:123], v[162:165], v[178:181], v[120:123]
	v_mfma_f32_16x16x32_bf16 v[124:127], v[214:217], v[178:181], v[124:127]
	v_mfma_f32_16x16x32_bf16 v[68:71], v[218:221], v[178:181], v[68:71]
	s_waitcnt lgkmcnt(1)
	v_mfma_f32_16x16x32_bf16 v[128:131], v[158:161], v[222:225], v[128:131]
	v_mfma_f32_16x16x32_bf16 v[132:135], v[162:165], v[222:225], v[132:135]
	v_mfma_f32_16x16x32_bf16 v[136:139], v[214:217], v[222:225], v[136:139]
	v_mfma_f32_16x16x32_bf16 v[84:87], v[218:221], v[222:225], v[84:87]
	s_waitcnt lgkmcnt(0)
	v_mfma_f32_16x16x32_bf16 v[100:103], v[158:161], v[226:229], v[100:103]
	v_mfma_f32_16x16x32_bf16 v[140:143], v[162:165], v[226:229], v[140:143]
	v_mfma_f32_16x16x32_bf16 v[150:153], v[214:217], v[226:229], v[150:153]
	v_mfma_f32_16x16x32_bf16 v[154:157], v[218:221], v[226:229], v[154:157]
	s_add_u32 s46, s0, 0x2380
	s_addc_u32 s47, s1, 0
	s_add_u32 s48, s14, 0x2380
	s_waitcnt vmcnt(0)
	s_barrier
	s_addc_u32 s49, s15, 0
	ds_read_b128 v[158:161], v7 offset:32768
	ds_read_b128 v[162:165], v6
	ds_read_b128 v[166:169], v7 offset:34816
	ds_read_b128 v[178:181], v6 offset:2048
	ds_read_b128 v[214:217], v7 offset:36864
	ds_read_b128 v[218:221], v7 offset:38912
	ds_read_b128 v[222:225], v6 offset:4096
	ds_read_b128 v[226:229], v6 offset:6144
	s_waitcnt lgkmcnt(6)
	v_mfma_f32_16x16x32_bf16 v[40:43], v[158:161], v[162:165], v[40:43]
	s_waitcnt lgkmcnt(5)
	v_mfma_f32_16x16x32_bf16 v[44:47], v[166:169], v[162:165], v[44:47]
	s_waitcnt lgkmcnt(4)
	v_mfma_f32_16x16x32_bf16 v[56:59], v[158:161], v[178:181], v[56:59]
	s_mov_b32 m0, s38
	v_mfma_f32_16x16x32_bf16 v[60:63], v[166:169], v[178:181], v[60:63]
	global_load_lds_dwordx4 v0, s[46:47]
	s_waitcnt lgkmcnt(3)
	v_mfma_f32_16x16x32_bf16 v[48:51], v[214:217], v[162:165], v[48:51]
	v_mfma_f32_16x16x32_bf16 v[64:67], v[214:217], v[178:181], v[64:67]
	s_waitcnt lgkmcnt(2)
	v_mfma_f32_16x16x32_bf16 v[174:177], v[218:221], v[162:165], v[174:177]
	ds_read_b128 v[162:165], v6 offset:8192
	v_mfma_f32_16x16x32_bf16 v[170:173], v[218:221], v[178:181], v[170:173]
	ds_read_b128 v[178:181], v6 offset:10240
	s_waitcnt lgkmcnt(3)
	s_mov_b32 m0, s37
	v_mfma_f32_16x16x32_bf16 v[72:75], v[158:161], v[222:225], v[72:75]
	global_load_lds_dwordx4 v0, s[48:49]
	v_mfma_f32_16x16x32_bf16 v[76:79], v[166:169], v[222:225], v[76:79]
	v_mfma_f32_16x16x32_bf16 v[80:83], v[214:217], v[222:225], v[80:83]
	v_mfma_f32_16x16x32_bf16 v[32:35], v[218:221], v[222:225], v[32:35]
	ds_read_b128 v[222:225], v6 offset:12288
	s_waitcnt lgkmcnt(3)
	v_mfma_f32_16x16x32_bf16 v[88:91], v[158:161], v[226:229], v[88:91]
	s_mov_b32 m0, s39
	v_mfma_f32_16x16x32_bf16 v[92:95], v[166:169], v[226:229], v[92:95]
	global_load_lds_dwordx4 v2, s[46:47]
	v_mfma_f32_16x16x32_bf16 v[96:99], v[214:217], v[226:229], v[96:99]
	v_mfma_f32_16x16x32_bf16 v[36:39], v[218:221], v[226:229], v[36:39]
	ds_read_b128 v[226:229], v6 offset:14336
	s_waitcnt lgkmcnt(3)
	v_mfma_f32_16x16x32_bf16 v[104:107], v[158:161], v[162:165], v[104:107]
	s_waitcnt lgkmcnt(2)
	v_mfma_f32_16x16x32_bf16 v[116:119], v[158:161], v[178:181], v[116:119]
	s_waitcnt lgkmcnt(1)
	s_mov_b32 m0, s40
	v_mfma_f32_16x16x32_bf16 v[128:131], v[158:161], v[222:225], v[128:131]
	global_load_lds_dwordx4 v2, s[48:49]
	s_waitcnt lgkmcnt(0)
	v_mfma_f32_16x16x32_bf16 v[100:103], v[158:161], v[226:229], v[100:103]
	ds_read_b128 v[158:161], v7 offset:33792
	v_mfma_f32_16x16x32_bf16 v[108:111], v[166:169], v[162:165], v[108:111]
	v_mfma_f32_16x16x32_bf16 v[120:123], v[166:169], v[178:181], v[120:123]
	v_mfma_f32_16x16x32_bf16 v[132:135], v[166:169], v[222:225], v[132:135]
	s_mov_b32 m0, s41
	v_mfma_f32_16x16x32_bf16 v[140:143], v[166:169], v[226:229], v[140:143]
	global_load_lds_dwordx4 v4, s[46:47]
	ds_read_b128 v[166:169], v6 offset:1024
	v_mfma_f32_16x16x32_bf16 v[112:115], v[214:217], v[162:165], v[112:115]
	v_mfma_f32_16x16x32_bf16 v[52:55], v[218:221], v[162:165], v[52:55]
	ds_read_b128 v[162:165], v7 offset:35840
	v_mfma_f32_16x16x32_bf16 v[124:127], v[214:217], v[178:181], v[124:127]
	v_mfma_f32_16x16x32_bf16 v[68:71], v[218:221], v[178:181], v[68:71]
	ds_read_b128 v[178:181], v6 offset:3072
	s_mov_b32 m0, s42
	v_mfma_f32_16x16x32_bf16 v[136:139], v[214:217], v[222:225], v[136:139]
	global_load_lds_dwordx4 v4, s[48:49]
	v_mfma_f32_16x16x32_bf16 v[84:87], v[218:221], v[222:225], v[84:87]
	ds_read_b128 v[222:225], v6 offset:5120
	v_mfma_f32_16x16x32_bf16 v[150:153], v[214:217], v[226:229], v[150:153]
	ds_read_b128 v[214:217], v7 offset:37888
	v_mfma_f32_16x16x32_bf16 v[154:157], v[218:221], v[226:229], v[154:157]
	ds_read_b128 v[218:221], v7 offset:39936
	ds_read_b128 v[226:229], v6 offset:7168
	s_waitcnt lgkmcnt(6)
	v_mfma_f32_16x16x32_bf16 v[40:43], v[158:161], v[166:169], v[40:43]
	s_waitcnt lgkmcnt(5)
	s_mov_b32 m0, s43
	v_mfma_f32_16x16x32_bf16 v[44:47], v[162:165], v[166:169], v[44:47]
	global_load_lds_dwordx4 v146, s[46:47]
	s_waitcnt lgkmcnt(4)
	v_mfma_f32_16x16x32_bf16 v[56:59], v[158:161], v[178:181], v[56:59]
	v_mfma_f32_16x16x32_bf16 v[60:63], v[162:165], v[178:181], v[60:63]
	s_waitcnt lgkmcnt(3)
	v_mfma_f32_16x16x32_bf16 v[72:75], v[158:161], v[222:225], v[72:75]
	v_mfma_f32_16x16x32_bf16 v[76:79], v[162:165], v[222:225], v[76:79]
	s_waitcnt lgkmcnt(2)
	s_mov_b32 m0, s44
	v_mfma_f32_16x16x32_bf16 v[48:51], v[214:217], v[166:169], v[48:51]
	global_load_lds_dwordx4 v146, s[48:49]
	s_waitcnt lgkmcnt(1)
	v_mfma_f32_16x16x32_bf16 v[174:177], v[218:221], v[166:169], v[174:177]
	ds_read_b128 v[166:169], v6 offset:9216
	v_mfma_f32_16x16x32_bf16 v[64:67], v[214:217], v[178:181], v[64:67]
	v_mfma_f32_16x16x32_bf16 v[170:173], v[218:221], v[178:181], v[170:173]
	ds_read_b128 v[178:181], v6 offset:11264
	v_mfma_f32_16x16x32_bf16 v[80:83], v[214:217], v[222:225], v[80:83]
	v_mfma_f32_16x16x32_bf16 v[32:35], v[218:221], v[222:225], v[32:35]
	ds_read_b128 v[222:225], v6 offset:13312
	s_waitcnt lgkmcnt(3)
	v_mfma_f32_16x16x32_bf16 v[88:91], v[158:161], v[226:229], v[88:91]
	v_mfma_f32_16x16x32_bf16 v[92:95], v[162:165], v[226:229], v[92:95]
	v_mfma_f32_16x16x32_bf16 v[96:99], v[214:217], v[226:229], v[96:99]
	v_mfma_f32_16x16x32_bf16 v[36:39], v[218:221], v[226:229], v[36:39]
	ds_read_b128 v[226:229], v6 offset:15360
	s_waitcnt lgkmcnt(3)
	v_mfma_f32_16x16x32_bf16 v[104:107], v[158:161], v[166:169], v[104:107]
	v_mfma_f32_16x16x32_bf16 v[108:111], v[162:165], v[166:169], v[108:111]
	v_mfma_f32_16x16x32_bf16 v[112:115], v[214:217], v[166:169], v[112:115]
	v_mfma_f32_16x16x32_bf16 v[52:55], v[218:221], v[166:169], v[52:55]
	s_waitcnt lgkmcnt(2)
	v_mfma_f32_16x16x32_bf16 v[116:119], v[158:161], v[178:181], v[116:119]
	v_mfma_f32_16x16x32_bf16 v[120:123], v[162:165], v[178:181], v[120:123]
	v_mfma_f32_16x16x32_bf16 v[124:127], v[214:217], v[178:181], v[124:127]
	v_mfma_f32_16x16x32_bf16 v[68:71], v[218:221], v[178:181], v[68:71]
	s_waitcnt lgkmcnt(1)
	v_mfma_f32_16x16x32_bf16 v[128:131], v[158:161], v[222:225], v[128:131]
	v_mfma_f32_16x16x32_bf16 v[132:135], v[162:165], v[222:225], v[132:135]
	v_mfma_f32_16x16x32_bf16 v[136:139], v[214:217], v[222:225], v[136:139]
	v_mfma_f32_16x16x32_bf16 v[84:87], v[218:221], v[222:225], v[84:87]
	s_waitcnt lgkmcnt(0)
	v_mfma_f32_16x16x32_bf16 v[100:103], v[158:161], v[226:229], v[100:103]
	v_mfma_f32_16x16x32_bf16 v[140:143], v[162:165], v[226:229], v[140:143]
	v_mfma_f32_16x16x32_bf16 v[150:153], v[214:217], v[226:229], v[150:153]
	v_mfma_f32_16x16x32_bf16 v[154:157], v[218:221], v[226:229], v[154:157]
	s_add_u32 s46, s0, 0x2400
	s_addc_u32 s47, s1, 0
	s_add_u32 s48, s14, 0x2400
	s_waitcnt vmcnt(0)
	s_barrier
	s_addc_u32 s49, s15, 0
	ds_read_b128 v[158:161], v8
	ds_read_b128 v[162:165], v12
	ds_read_b128 v[166:169], v9
	ds_read_b128 v[178:181], v13
	ds_read_b128 v[214:217], v11
	ds_read_b128 v[218:221], v10
	ds_read_b128 v[222:225], v14
	ds_read_b128 v[226:229], v15
	s_waitcnt lgkmcnt(6)
	v_mfma_f32_16x16x32_bf16 v[40:43], v[158:161], v[162:165], v[40:43]
	s_waitcnt lgkmcnt(5)
	v_mfma_f32_16x16x32_bf16 v[44:47], v[166:169], v[162:165], v[44:47]
	s_waitcnt lgkmcnt(4)
	v_mfma_f32_16x16x32_bf16 v[56:59], v[158:161], v[178:181], v[56:59]
	s_mov_b32 m0, s27
	v_mfma_f32_16x16x32_bf16 v[60:63], v[166:169], v[178:181], v[60:63]
	global_load_lds_dwordx4 v0, s[46:47]
	s_waitcnt lgkmcnt(3)
	v_mfma_f32_16x16x32_bf16 v[48:51], v[214:217], v[162:165], v[48:51]
	v_mfma_f32_16x16x32_bf16 v[64:67], v[214:217], v[178:181], v[64:67]
	s_waitcnt lgkmcnt(2)
	v_mfma_f32_16x16x32_bf16 v[174:177], v[218:221], v[162:165], v[174:177]
	ds_read_b128 v[162:165], v16
	v_mfma_f32_16x16x32_bf16 v[170:173], v[218:221], v[178:181], v[170:173]
	ds_read_b128 v[178:181], v17
	s_waitcnt lgkmcnt(3)
	s_mov_b32 m0, s28
	v_mfma_f32_16x16x32_bf16 v[72:75], v[158:161], v[222:225], v[72:75]
	global_load_lds_dwordx4 v0, s[48:49]
	v_mfma_f32_16x16x32_bf16 v[76:79], v[166:169], v[222:225], v[76:79]
	v_mfma_f32_16x16x32_bf16 v[80:83], v[214:217], v[222:225], v[80:83]
	v_mfma_f32_16x16x32_bf16 v[32:35], v[218:221], v[222:225], v[32:35]
	ds_read_b128 v[222:225], v18
	s_waitcnt lgkmcnt(3)
	v_mfma_f32_16x16x32_bf16 v[88:91], v[158:161], v[226:229], v[88:91]
	s_mov_b32 m0, s29
	v_mfma_f32_16x16x32_bf16 v[92:95], v[166:169], v[226:229], v[92:95]
	global_load_lds_dwordx4 v2, s[46:47]
	v_mfma_f32_16x16x32_bf16 v[96:99], v[214:217], v[226:229], v[96:99]
	v_mfma_f32_16x16x32_bf16 v[36:39], v[218:221], v[226:229], v[36:39]
	ds_read_b128 v[226:229], v19
	s_waitcnt lgkmcnt(3)
	v_mfma_f32_16x16x32_bf16 v[104:107], v[158:161], v[162:165], v[104:107]
	s_waitcnt lgkmcnt(2)
	v_mfma_f32_16x16x32_bf16 v[116:119], v[158:161], v[178:181], v[116:119]
	s_waitcnt lgkmcnt(1)
	s_mov_b32 m0, s30
	v_mfma_f32_16x16x32_bf16 v[128:131], v[158:161], v[222:225], v[128:131]
	global_load_lds_dwordx4 v2, s[48:49]
	s_waitcnt lgkmcnt(0)
	v_mfma_f32_16x16x32_bf16 v[100:103], v[158:161], v[226:229], v[100:103]
	ds_read_b128 v[158:161], v20
	v_mfma_f32_16x16x32_bf16 v[108:111], v[166:169], v[162:165], v[108:111]
	v_mfma_f32_16x16x32_bf16 v[120:123], v[166:169], v[178:181], v[120:123]
	v_mfma_f32_16x16x32_bf16 v[132:135], v[166:169], v[222:225], v[132:135]
	s_mov_b32 m0, s31
	v_mfma_f32_16x16x32_bf16 v[140:143], v[166:169], v[226:229], v[140:143]
	global_load_lds_dwordx4 v4, s[46:47]
	ds_read_b128 v[166:169], v24
	v_mfma_f32_16x16x32_bf16 v[112:115], v[214:217], v[162:165], v[112:115]
	v_mfma_f32_16x16x32_bf16 v[52:55], v[218:221], v[162:165], v[52:55]
	ds_read_b128 v[162:165], v21
	v_mfma_f32_16x16x32_bf16 v[124:127], v[214:217], v[178:181], v[124:127]
	v_mfma_f32_16x16x32_bf16 v[68:71], v[218:221], v[178:181], v[68:71]
	ds_read_b128 v[178:181], v25
	s_mov_b32 m0, s34
	v_mfma_f32_16x16x32_bf16 v[136:139], v[214:217], v[222:225], v[136:139]
	global_load_lds_dwordx4 v4, s[48:49]
	v_mfma_f32_16x16x32_bf16 v[84:87], v[218:221], v[222:225], v[84:87]
	ds_read_b128 v[222:225], v26
	v_mfma_f32_16x16x32_bf16 v[150:153], v[214:217], v[226:229], v[150:153]
	ds_read_b128 v[214:217], v23
	v_mfma_f32_16x16x32_bf16 v[154:157], v[218:221], v[226:229], v[154:157]
	ds_read_b128 v[218:221], v22
	ds_read_b128 v[226:229], v27
	s_waitcnt lgkmcnt(6)
	v_mfma_f32_16x16x32_bf16 v[40:43], v[158:161], v[166:169], v[40:43]
	s_waitcnt lgkmcnt(5)
	s_mov_b32 m0, s35
	v_mfma_f32_16x16x32_bf16 v[44:47], v[162:165], v[166:169], v[44:47]
	global_load_lds_dwordx4 v146, s[46:47]
	s_waitcnt lgkmcnt(4)
	v_mfma_f32_16x16x32_bf16 v[56:59], v[158:161], v[178:181], v[56:59]
	v_mfma_f32_16x16x32_bf16 v[60:63], v[162:165], v[178:181], v[60:63]
	s_waitcnt lgkmcnt(3)
	v_mfma_f32_16x16x32_bf16 v[72:75], v[158:161], v[222:225], v[72:75]
	v_mfma_f32_16x16x32_bf16 v[76:79], v[162:165], v[222:225], v[76:79]
	s_waitcnt lgkmcnt(2)
	s_mov_b32 m0, s36
	v_mfma_f32_16x16x32_bf16 v[48:51], v[214:217], v[166:169], v[48:51]
	global_load_lds_dwordx4 v146, s[48:49]
	s_waitcnt lgkmcnt(1)
	v_mfma_f32_16x16x32_bf16 v[174:177], v[218:221], v[166:169], v[174:177]
	ds_read_b128 v[166:169], v28
	v_mfma_f32_16x16x32_bf16 v[64:67], v[214:217], v[178:181], v[64:67]
	v_mfma_f32_16x16x32_bf16 v[170:173], v[218:221], v[178:181], v[170:173]
	ds_read_b128 v[178:181], v29
	v_mfma_f32_16x16x32_bf16 v[80:83], v[214:217], v[222:225], v[80:83]
	v_mfma_f32_16x16x32_bf16 v[32:35], v[218:221], v[222:225], v[32:35]
	ds_read_b128 v[222:225], v30
	s_waitcnt lgkmcnt(3)
	v_mfma_f32_16x16x32_bf16 v[88:91], v[158:161], v[226:229], v[88:91]
	v_mfma_f32_16x16x32_bf16 v[92:95], v[162:165], v[226:229], v[92:95]
	v_mfma_f32_16x16x32_bf16 v[96:99], v[214:217], v[226:229], v[96:99]
	v_mfma_f32_16x16x32_bf16 v[36:39], v[218:221], v[226:229], v[36:39]
	ds_read_b128 v[226:229], v31
	s_waitcnt lgkmcnt(3)
	v_mfma_f32_16x16x32_bf16 v[104:107], v[158:161], v[166:169], v[104:107]
	v_mfma_f32_16x16x32_bf16 v[108:111], v[162:165], v[166:169], v[108:111]
	v_mfma_f32_16x16x32_bf16 v[112:115], v[214:217], v[166:169], v[112:115]
	v_mfma_f32_16x16x32_bf16 v[52:55], v[218:221], v[166:169], v[52:55]
	s_waitcnt lgkmcnt(2)
	v_mfma_f32_16x16x32_bf16 v[116:119], v[158:161], v[178:181], v[116:119]
	v_mfma_f32_16x16x32_bf16 v[120:123], v[162:165], v[178:181], v[120:123]
	v_mfma_f32_16x16x32_bf16 v[124:127], v[214:217], v[178:181], v[124:127]
	v_mfma_f32_16x16x32_bf16 v[68:71], v[218:221], v[178:181], v[68:71]
	s_waitcnt lgkmcnt(1)
	v_mfma_f32_16x16x32_bf16 v[128:131], v[158:161], v[222:225], v[128:131]
	v_mfma_f32_16x16x32_bf16 v[132:135], v[162:165], v[222:225], v[132:135]
	v_mfma_f32_16x16x32_bf16 v[136:139], v[214:217], v[222:225], v[136:139]
	v_mfma_f32_16x16x32_bf16 v[84:87], v[218:221], v[222:225], v[84:87]
	s_waitcnt lgkmcnt(0)
	v_mfma_f32_16x16x32_bf16 v[100:103], v[158:161], v[226:229], v[100:103]
	v_mfma_f32_16x16x32_bf16 v[140:143], v[162:165], v[226:229], v[140:143]
	v_mfma_f32_16x16x32_bf16 v[150:153], v[214:217], v[226:229], v[150:153]
	v_mfma_f32_16x16x32_bf16 v[154:157], v[218:221], v[226:229], v[154:157]
	s_add_u32 s46, s0, 0x2480
	s_addc_u32 s47, s1, 0
	s_add_u32 s48, s14, 0x2480
	s_waitcnt vmcnt(0)
	s_barrier
	s_addc_u32 s49, s15, 0
	ds_read_b128 v[158:161], v7 offset:32768
	ds_read_b128 v[162:165], v6
	ds_read_b128 v[166:169], v7 offset:34816
	ds_read_b128 v[178:181], v6 offset:2048
	ds_read_b128 v[214:217], v7 offset:36864
	ds_read_b128 v[218:221], v7 offset:38912
	ds_read_b128 v[222:225], v6 offset:4096
	ds_read_b128 v[226:229], v6 offset:6144
	s_waitcnt lgkmcnt(6)
	v_mfma_f32_16x16x32_bf16 v[40:43], v[158:161], v[162:165], v[40:43]
	s_waitcnt lgkmcnt(5)
	v_mfma_f32_16x16x32_bf16 v[44:47], v[166:169], v[162:165], v[44:47]
	s_waitcnt lgkmcnt(4)
	v_mfma_f32_16x16x32_bf16 v[56:59], v[158:161], v[178:181], v[56:59]
	s_mov_b32 m0, s38
	v_mfma_f32_16x16x32_bf16 v[60:63], v[166:169], v[178:181], v[60:63]
	global_load_lds_dwordx4 v0, s[46:47]
	s_waitcnt lgkmcnt(3)
	v_mfma_f32_16x16x32_bf16 v[48:51], v[214:217], v[162:165], v[48:51]
	v_mfma_f32_16x16x32_bf16 v[64:67], v[214:217], v[178:181], v[64:67]
	s_waitcnt lgkmcnt(2)
	v_mfma_f32_16x16x32_bf16 v[174:177], v[218:221], v[162:165], v[174:177]
	ds_read_b128 v[162:165], v6 offset:8192
	v_mfma_f32_16x16x32_bf16 v[170:173], v[218:221], v[178:181], v[170:173]
	ds_read_b128 v[178:181], v6 offset:10240
	s_waitcnt lgkmcnt(3)
	s_mov_b32 m0, s37
	v_mfma_f32_16x16x32_bf16 v[72:75], v[158:161], v[222:225], v[72:75]
	global_load_lds_dwordx4 v0, s[48:49]
	v_mfma_f32_16x16x32_bf16 v[76:79], v[166:169], v[222:225], v[76:79]
	v_mfma_f32_16x16x32_bf16 v[80:83], v[214:217], v[222:225], v[80:83]
	v_mfma_f32_16x16x32_bf16 v[32:35], v[218:221], v[222:225], v[32:35]
	ds_read_b128 v[222:225], v6 offset:12288
	s_waitcnt lgkmcnt(3)
	v_mfma_f32_16x16x32_bf16 v[88:91], v[158:161], v[226:229], v[88:91]
	s_mov_b32 m0, s39
	v_mfma_f32_16x16x32_bf16 v[92:95], v[166:169], v[226:229], v[92:95]
	global_load_lds_dwordx4 v2, s[46:47]
	v_mfma_f32_16x16x32_bf16 v[96:99], v[214:217], v[226:229], v[96:99]
	v_mfma_f32_16x16x32_bf16 v[36:39], v[218:221], v[226:229], v[36:39]
	ds_read_b128 v[226:229], v6 offset:14336
	s_waitcnt lgkmcnt(3)
	v_mfma_f32_16x16x32_bf16 v[104:107], v[158:161], v[162:165], v[104:107]
	s_waitcnt lgkmcnt(2)
	v_mfma_f32_16x16x32_bf16 v[116:119], v[158:161], v[178:181], v[116:119]
	s_waitcnt lgkmcnt(1)
	s_mov_b32 m0, s40
	v_mfma_f32_16x16x32_bf16 v[128:131], v[158:161], v[222:225], v[128:131]
	global_load_lds_dwordx4 v2, s[48:49]
	s_waitcnt lgkmcnt(0)
	v_mfma_f32_16x16x32_bf16 v[100:103], v[158:161], v[226:229], v[100:103]
	ds_read_b128 v[158:161], v7 offset:33792
	v_mfma_f32_16x16x32_bf16 v[108:111], v[166:169], v[162:165], v[108:111]
	v_mfma_f32_16x16x32_bf16 v[120:123], v[166:169], v[178:181], v[120:123]
	v_mfma_f32_16x16x32_bf16 v[132:135], v[166:169], v[222:225], v[132:135]
	s_mov_b32 m0, s41
	v_mfma_f32_16x16x32_bf16 v[140:143], v[166:169], v[226:229], v[140:143]
	global_load_lds_dwordx4 v4, s[46:47]
	ds_read_b128 v[166:169], v6 offset:1024
	v_mfma_f32_16x16x32_bf16 v[112:115], v[214:217], v[162:165], v[112:115]
	v_mfma_f32_16x16x32_bf16 v[52:55], v[218:221], v[162:165], v[52:55]
	ds_read_b128 v[162:165], v7 offset:35840
	v_mfma_f32_16x16x32_bf16 v[124:127], v[214:217], v[178:181], v[124:127]
	v_mfma_f32_16x16x32_bf16 v[68:71], v[218:221], v[178:181], v[68:71]
	ds_read_b128 v[178:181], v6 offset:3072
	s_mov_b32 m0, s42
	v_mfma_f32_16x16x32_bf16 v[136:139], v[214:217], v[222:225], v[136:139]
	global_load_lds_dwordx4 v4, s[48:49]
	v_mfma_f32_16x16x32_bf16 v[84:87], v[218:221], v[222:225], v[84:87]
	ds_read_b128 v[222:225], v6 offset:5120
	v_mfma_f32_16x16x32_bf16 v[150:153], v[214:217], v[226:229], v[150:153]
	ds_read_b128 v[214:217], v7 offset:37888
	v_mfma_f32_16x16x32_bf16 v[154:157], v[218:221], v[226:229], v[154:157]
	ds_read_b128 v[218:221], v7 offset:39936
	ds_read_b128 v[226:229], v6 offset:7168
	s_waitcnt lgkmcnt(6)
	v_mfma_f32_16x16x32_bf16 v[40:43], v[158:161], v[166:169], v[40:43]
	s_waitcnt lgkmcnt(5)
	s_mov_b32 m0, s43
	v_mfma_f32_16x16x32_bf16 v[44:47], v[162:165], v[166:169], v[44:47]
	global_load_lds_dwordx4 v146, s[46:47]
	s_waitcnt lgkmcnt(4)
	v_mfma_f32_16x16x32_bf16 v[56:59], v[158:161], v[178:181], v[56:59]
	v_mfma_f32_16x16x32_bf16 v[60:63], v[162:165], v[178:181], v[60:63]
	s_waitcnt lgkmcnt(3)
	v_mfma_f32_16x16x32_bf16 v[72:75], v[158:161], v[222:225], v[72:75]
	v_mfma_f32_16x16x32_bf16 v[76:79], v[162:165], v[222:225], v[76:79]
	s_waitcnt lgkmcnt(2)
	s_mov_b32 m0, s44
	v_mfma_f32_16x16x32_bf16 v[48:51], v[214:217], v[166:169], v[48:51]
	global_load_lds_dwordx4 v146, s[48:49]
	s_waitcnt lgkmcnt(1)
	v_mfma_f32_16x16x32_bf16 v[174:177], v[218:221], v[166:169], v[174:177]
	ds_read_b128 v[166:169], v6 offset:9216
	v_mfma_f32_16x16x32_bf16 v[64:67], v[214:217], v[178:181], v[64:67]
	v_mfma_f32_16x16x32_bf16 v[170:173], v[218:221], v[178:181], v[170:173]
	ds_read_b128 v[178:181], v6 offset:11264
	v_mfma_f32_16x16x32_bf16 v[80:83], v[214:217], v[222:225], v[80:83]
	v_mfma_f32_16x16x32_bf16 v[32:35], v[218:221], v[222:225], v[32:35]
	ds_read_b128 v[222:225], v6 offset:13312
	s_waitcnt lgkmcnt(3)
	v_mfma_f32_16x16x32_bf16 v[88:91], v[158:161], v[226:229], v[88:91]
	v_mfma_f32_16x16x32_bf16 v[92:95], v[162:165], v[226:229], v[92:95]
	v_mfma_f32_16x16x32_bf16 v[96:99], v[214:217], v[226:229], v[96:99]
	v_mfma_f32_16x16x32_bf16 v[36:39], v[218:221], v[226:229], v[36:39]
	ds_read_b128 v[226:229], v6 offset:15360
	s_waitcnt lgkmcnt(3)
	v_mfma_f32_16x16x32_bf16 v[104:107], v[158:161], v[166:169], v[104:107]
	v_mfma_f32_16x16x32_bf16 v[108:111], v[162:165], v[166:169], v[108:111]
	v_mfma_f32_16x16x32_bf16 v[112:115], v[214:217], v[166:169], v[112:115]
	v_mfma_f32_16x16x32_bf16 v[52:55], v[218:221], v[166:169], v[52:55]
	s_waitcnt lgkmcnt(2)
	v_mfma_f32_16x16x32_bf16 v[116:119], v[158:161], v[178:181], v[116:119]
	v_mfma_f32_16x16x32_bf16 v[120:123], v[162:165], v[178:181], v[120:123]
	v_mfma_f32_16x16x32_bf16 v[124:127], v[214:217], v[178:181], v[124:127]
	v_mfma_f32_16x16x32_bf16 v[68:71], v[218:221], v[178:181], v[68:71]
	s_waitcnt lgkmcnt(1)
	v_mfma_f32_16x16x32_bf16 v[128:131], v[158:161], v[222:225], v[128:131]
	v_mfma_f32_16x16x32_bf16 v[132:135], v[162:165], v[222:225], v[132:135]
	v_mfma_f32_16x16x32_bf16 v[136:139], v[214:217], v[222:225], v[136:139]
	v_mfma_f32_16x16x32_bf16 v[84:87], v[218:221], v[222:225], v[84:87]
	s_waitcnt lgkmcnt(0)
	v_mfma_f32_16x16x32_bf16 v[100:103], v[158:161], v[226:229], v[100:103]
	v_mfma_f32_16x16x32_bf16 v[140:143], v[162:165], v[226:229], v[140:143]
	v_mfma_f32_16x16x32_bf16 v[150:153], v[214:217], v[226:229], v[150:153]
	v_mfma_f32_16x16x32_bf16 v[154:157], v[218:221], v[226:229], v[154:157]
	s_add_u32 s46, s0, 0x2500
	s_addc_u32 s47, s1, 0
	s_add_u32 s48, s14, 0x2500
	s_waitcnt vmcnt(0)
	s_barrier
	s_addc_u32 s49, s15, 0
	ds_read_b128 v[158:161], v8
	ds_read_b128 v[162:165], v12
	ds_read_b128 v[166:169], v9
	ds_read_b128 v[178:181], v13
	ds_read_b128 v[214:217], v11
	ds_read_b128 v[218:221], v10
	ds_read_b128 v[222:225], v14
	ds_read_b128 v[226:229], v15
	s_waitcnt lgkmcnt(6)
	v_mfma_f32_16x16x32_bf16 v[40:43], v[158:161], v[162:165], v[40:43]
	s_waitcnt lgkmcnt(5)
	v_mfma_f32_16x16x32_bf16 v[44:47], v[166:169], v[162:165], v[44:47]
	s_waitcnt lgkmcnt(4)
	v_mfma_f32_16x16x32_bf16 v[56:59], v[158:161], v[178:181], v[56:59]
	s_mov_b32 m0, s27
	v_mfma_f32_16x16x32_bf16 v[60:63], v[166:169], v[178:181], v[60:63]
	global_load_lds_dwordx4 v0, s[46:47]
	s_waitcnt lgkmcnt(3)
	v_mfma_f32_16x16x32_bf16 v[48:51], v[214:217], v[162:165], v[48:51]
	v_mfma_f32_16x16x32_bf16 v[64:67], v[214:217], v[178:181], v[64:67]
	s_waitcnt lgkmcnt(2)
	v_mfma_f32_16x16x32_bf16 v[174:177], v[218:221], v[162:165], v[174:177]
	ds_read_b128 v[162:165], v16
	v_mfma_f32_16x16x32_bf16 v[170:173], v[218:221], v[178:181], v[170:173]
	ds_read_b128 v[178:181], v17
	s_waitcnt lgkmcnt(3)
	s_mov_b32 m0, s28
	v_mfma_f32_16x16x32_bf16 v[72:75], v[158:161], v[222:225], v[72:75]
	global_load_lds_dwordx4 v0, s[48:49]
	v_mfma_f32_16x16x32_bf16 v[76:79], v[166:169], v[222:225], v[76:79]
	v_mfma_f32_16x16x32_bf16 v[80:83], v[214:217], v[222:225], v[80:83]
	v_mfma_f32_16x16x32_bf16 v[32:35], v[218:221], v[222:225], v[32:35]
	ds_read_b128 v[222:225], v18
	s_waitcnt lgkmcnt(3)
	v_mfma_f32_16x16x32_bf16 v[88:91], v[158:161], v[226:229], v[88:91]
	s_mov_b32 m0, s29
	v_mfma_f32_16x16x32_bf16 v[92:95], v[166:169], v[226:229], v[92:95]
	global_load_lds_dwordx4 v2, s[46:47]
	v_mfma_f32_16x16x32_bf16 v[96:99], v[214:217], v[226:229], v[96:99]
	v_mfma_f32_16x16x32_bf16 v[36:39], v[218:221], v[226:229], v[36:39]
	ds_read_b128 v[226:229], v19
	s_waitcnt lgkmcnt(3)
	v_mfma_f32_16x16x32_bf16 v[104:107], v[158:161], v[162:165], v[104:107]
	s_waitcnt lgkmcnt(2)
	v_mfma_f32_16x16x32_bf16 v[116:119], v[158:161], v[178:181], v[116:119]
	s_waitcnt lgkmcnt(1)
	s_mov_b32 m0, s30
	v_mfma_f32_16x16x32_bf16 v[128:131], v[158:161], v[222:225], v[128:131]
	global_load_lds_dwordx4 v2, s[48:49]
	s_waitcnt lgkmcnt(0)
	v_mfma_f32_16x16x32_bf16 v[100:103], v[158:161], v[226:229], v[100:103]
	ds_read_b128 v[158:161], v20
	v_mfma_f32_16x16x32_bf16 v[108:111], v[166:169], v[162:165], v[108:111]
	v_mfma_f32_16x16x32_bf16 v[120:123], v[166:169], v[178:181], v[120:123]
	v_mfma_f32_16x16x32_bf16 v[132:135], v[166:169], v[222:225], v[132:135]
	s_mov_b32 m0, s31
	v_mfma_f32_16x16x32_bf16 v[140:143], v[166:169], v[226:229], v[140:143]
	global_load_lds_dwordx4 v4, s[46:47]
	ds_read_b128 v[166:169], v24
	v_mfma_f32_16x16x32_bf16 v[112:115], v[214:217], v[162:165], v[112:115]
	v_mfma_f32_16x16x32_bf16 v[52:55], v[218:221], v[162:165], v[52:55]
	ds_read_b128 v[162:165], v21
	v_mfma_f32_16x16x32_bf16 v[124:127], v[214:217], v[178:181], v[124:127]
	v_mfma_f32_16x16x32_bf16 v[68:71], v[218:221], v[178:181], v[68:71]
	ds_read_b128 v[178:181], v25
	s_mov_b32 m0, s34
	v_mfma_f32_16x16x32_bf16 v[136:139], v[214:217], v[222:225], v[136:139]
	global_load_lds_dwordx4 v4, s[48:49]
	v_mfma_f32_16x16x32_bf16 v[84:87], v[218:221], v[222:225], v[84:87]
	ds_read_b128 v[222:225], v26
	v_mfma_f32_16x16x32_bf16 v[150:153], v[214:217], v[226:229], v[150:153]
	ds_read_b128 v[214:217], v23
	v_mfma_f32_16x16x32_bf16 v[154:157], v[218:221], v[226:229], v[154:157]
	ds_read_b128 v[218:221], v22
	ds_read_b128 v[226:229], v27
	s_waitcnt lgkmcnt(6)
	v_mfma_f32_16x16x32_bf16 v[40:43], v[158:161], v[166:169], v[40:43]
	s_waitcnt lgkmcnt(5)
	s_mov_b32 m0, s35
	v_mfma_f32_16x16x32_bf16 v[44:47], v[162:165], v[166:169], v[44:47]
	global_load_lds_dwordx4 v146, s[46:47]
	s_waitcnt lgkmcnt(4)
	v_mfma_f32_16x16x32_bf16 v[56:59], v[158:161], v[178:181], v[56:59]
	v_mfma_f32_16x16x32_bf16 v[60:63], v[162:165], v[178:181], v[60:63]
	s_waitcnt lgkmcnt(3)
	v_mfma_f32_16x16x32_bf16 v[72:75], v[158:161], v[222:225], v[72:75]
	v_mfma_f32_16x16x32_bf16 v[76:79], v[162:165], v[222:225], v[76:79]
	s_waitcnt lgkmcnt(2)
	s_mov_b32 m0, s36
	v_mfma_f32_16x16x32_bf16 v[48:51], v[214:217], v[166:169], v[48:51]
	global_load_lds_dwordx4 v146, s[48:49]
	s_waitcnt lgkmcnt(1)
	v_mfma_f32_16x16x32_bf16 v[174:177], v[218:221], v[166:169], v[174:177]
	ds_read_b128 v[166:169], v28
	v_mfma_f32_16x16x32_bf16 v[64:67], v[214:217], v[178:181], v[64:67]
	v_mfma_f32_16x16x32_bf16 v[170:173], v[218:221], v[178:181], v[170:173]
	ds_read_b128 v[178:181], v29
	v_mfma_f32_16x16x32_bf16 v[80:83], v[214:217], v[222:225], v[80:83]
	v_mfma_f32_16x16x32_bf16 v[32:35], v[218:221], v[222:225], v[32:35]
	ds_read_b128 v[222:225], v30
	s_waitcnt lgkmcnt(3)
	v_mfma_f32_16x16x32_bf16 v[88:91], v[158:161], v[226:229], v[88:91]
	v_mfma_f32_16x16x32_bf16 v[92:95], v[162:165], v[226:229], v[92:95]
	v_mfma_f32_16x16x32_bf16 v[96:99], v[214:217], v[226:229], v[96:99]
	v_mfma_f32_16x16x32_bf16 v[36:39], v[218:221], v[226:229], v[36:39]
	ds_read_b128 v[226:229], v31
	s_waitcnt lgkmcnt(3)
	v_mfma_f32_16x16x32_bf16 v[104:107], v[158:161], v[166:169], v[104:107]
	v_mfma_f32_16x16x32_bf16 v[108:111], v[162:165], v[166:169], v[108:111]
	v_mfma_f32_16x16x32_bf16 v[112:115], v[214:217], v[166:169], v[112:115]
	v_mfma_f32_16x16x32_bf16 v[52:55], v[218:221], v[166:169], v[52:55]
	s_waitcnt lgkmcnt(2)
	v_mfma_f32_16x16x32_bf16 v[116:119], v[158:161], v[178:181], v[116:119]
	v_mfma_f32_16x16x32_bf16 v[120:123], v[162:165], v[178:181], v[120:123]
	v_mfma_f32_16x16x32_bf16 v[124:127], v[214:217], v[178:181], v[124:127]
	v_mfma_f32_16x16x32_bf16 v[68:71], v[218:221], v[178:181], v[68:71]
	s_waitcnt lgkmcnt(1)
	v_mfma_f32_16x16x32_bf16 v[128:131], v[158:161], v[222:225], v[128:131]
	v_mfma_f32_16x16x32_bf16 v[132:135], v[162:165], v[222:225], v[132:135]
	v_mfma_f32_16x16x32_bf16 v[136:139], v[214:217], v[222:225], v[136:139]
	v_mfma_f32_16x16x32_bf16 v[84:87], v[218:221], v[222:225], v[84:87]
	s_waitcnt lgkmcnt(0)
	v_mfma_f32_16x16x32_bf16 v[100:103], v[158:161], v[226:229], v[100:103]
	v_mfma_f32_16x16x32_bf16 v[140:143], v[162:165], v[226:229], v[140:143]
	v_mfma_f32_16x16x32_bf16 v[150:153], v[214:217], v[226:229], v[150:153]
	v_mfma_f32_16x16x32_bf16 v[154:157], v[218:221], v[226:229], v[154:157]
	s_add_u32 s46, s0, 0x2580
	s_addc_u32 s47, s1, 0
	s_add_u32 s48, s14, 0x2580
	s_waitcnt vmcnt(0)
	s_barrier
	s_addc_u32 s49, s15, 0
	ds_read_b128 v[158:161], v7 offset:32768
	ds_read_b128 v[162:165], v6
	ds_read_b128 v[166:169], v7 offset:34816
	ds_read_b128 v[178:181], v6 offset:2048
	ds_read_b128 v[214:217], v7 offset:36864
	ds_read_b128 v[218:221], v7 offset:38912
	ds_read_b128 v[222:225], v6 offset:4096
	ds_read_b128 v[226:229], v6 offset:6144
	s_waitcnt lgkmcnt(6)
	v_mfma_f32_16x16x32_bf16 v[40:43], v[158:161], v[162:165], v[40:43]
	s_waitcnt lgkmcnt(5)
	v_mfma_f32_16x16x32_bf16 v[44:47], v[166:169], v[162:165], v[44:47]
	s_waitcnt lgkmcnt(4)
	v_mfma_f32_16x16x32_bf16 v[56:59], v[158:161], v[178:181], v[56:59]
	s_mov_b32 m0, s38
	v_mfma_f32_16x16x32_bf16 v[60:63], v[166:169], v[178:181], v[60:63]
	global_load_lds_dwordx4 v0, s[46:47]
	s_waitcnt lgkmcnt(3)
	v_mfma_f32_16x16x32_bf16 v[48:51], v[214:217], v[162:165], v[48:51]
	v_mfma_f32_16x16x32_bf16 v[64:67], v[214:217], v[178:181], v[64:67]
	s_waitcnt lgkmcnt(2)
	v_mfma_f32_16x16x32_bf16 v[174:177], v[218:221], v[162:165], v[174:177]
	ds_read_b128 v[162:165], v6 offset:8192
	v_mfma_f32_16x16x32_bf16 v[170:173], v[218:221], v[178:181], v[170:173]
	ds_read_b128 v[178:181], v6 offset:10240
	s_waitcnt lgkmcnt(3)
	s_mov_b32 m0, s37
	v_mfma_f32_16x16x32_bf16 v[72:75], v[158:161], v[222:225], v[72:75]
	global_load_lds_dwordx4 v0, s[48:49]
	v_mfma_f32_16x16x32_bf16 v[76:79], v[166:169], v[222:225], v[76:79]
	v_mfma_f32_16x16x32_bf16 v[80:83], v[214:217], v[222:225], v[80:83]
	v_mfma_f32_16x16x32_bf16 v[32:35], v[218:221], v[222:225], v[32:35]
	ds_read_b128 v[222:225], v6 offset:12288
	s_waitcnt lgkmcnt(3)
	v_mfma_f32_16x16x32_bf16 v[88:91], v[158:161], v[226:229], v[88:91]
	s_mov_b32 m0, s39
	v_mfma_f32_16x16x32_bf16 v[92:95], v[166:169], v[226:229], v[92:95]
	global_load_lds_dwordx4 v2, s[46:47]
	v_mfma_f32_16x16x32_bf16 v[96:99], v[214:217], v[226:229], v[96:99]
	v_mfma_f32_16x16x32_bf16 v[36:39], v[218:221], v[226:229], v[36:39]
	ds_read_b128 v[226:229], v6 offset:14336
	s_waitcnt lgkmcnt(3)
	v_mfma_f32_16x16x32_bf16 v[104:107], v[158:161], v[162:165], v[104:107]
	s_waitcnt lgkmcnt(2)
	v_mfma_f32_16x16x32_bf16 v[116:119], v[158:161], v[178:181], v[116:119]
	s_waitcnt lgkmcnt(1)
	s_mov_b32 m0, s40
	v_mfma_f32_16x16x32_bf16 v[128:131], v[158:161], v[222:225], v[128:131]
	global_load_lds_dwordx4 v2, s[48:49]
	s_waitcnt lgkmcnt(0)
	v_mfma_f32_16x16x32_bf16 v[100:103], v[158:161], v[226:229], v[100:103]
	ds_read_b128 v[158:161], v7 offset:33792
	v_mfma_f32_16x16x32_bf16 v[108:111], v[166:169], v[162:165], v[108:111]
	v_mfma_f32_16x16x32_bf16 v[120:123], v[166:169], v[178:181], v[120:123]
	v_mfma_f32_16x16x32_bf16 v[132:135], v[166:169], v[222:225], v[132:135]
	s_mov_b32 m0, s41
	v_mfma_f32_16x16x32_bf16 v[140:143], v[166:169], v[226:229], v[140:143]
	global_load_lds_dwordx4 v4, s[46:47]
	ds_read_b128 v[166:169], v6 offset:1024
	v_mfma_f32_16x16x32_bf16 v[112:115], v[214:217], v[162:165], v[112:115]
	v_mfma_f32_16x16x32_bf16 v[52:55], v[218:221], v[162:165], v[52:55]
	ds_read_b128 v[162:165], v7 offset:35840
	v_mfma_f32_16x16x32_bf16 v[124:127], v[214:217], v[178:181], v[124:127]
	v_mfma_f32_16x16x32_bf16 v[68:71], v[218:221], v[178:181], v[68:71]
	ds_read_b128 v[178:181], v6 offset:3072
	s_mov_b32 m0, s42
	v_mfma_f32_16x16x32_bf16 v[136:139], v[214:217], v[222:225], v[136:139]
	global_load_lds_dwordx4 v4, s[48:49]
	v_mfma_f32_16x16x32_bf16 v[84:87], v[218:221], v[222:225], v[84:87]
	ds_read_b128 v[222:225], v6 offset:5120
	v_mfma_f32_16x16x32_bf16 v[150:153], v[214:217], v[226:229], v[150:153]
	ds_read_b128 v[214:217], v7 offset:37888
	v_mfma_f32_16x16x32_bf16 v[154:157], v[218:221], v[226:229], v[154:157]
	ds_read_b128 v[218:221], v7 offset:39936
	ds_read_b128 v[226:229], v6 offset:7168
	s_waitcnt lgkmcnt(6)
	v_mfma_f32_16x16x32_bf16 v[40:43], v[158:161], v[166:169], v[40:43]
	s_waitcnt lgkmcnt(5)
	s_mov_b32 m0, s43
	v_mfma_f32_16x16x32_bf16 v[44:47], v[162:165], v[166:169], v[44:47]
	global_load_lds_dwordx4 v146, s[46:47]
	s_waitcnt lgkmcnt(4)
	v_mfma_f32_16x16x32_bf16 v[56:59], v[158:161], v[178:181], v[56:59]
	v_mfma_f32_16x16x32_bf16 v[60:63], v[162:165], v[178:181], v[60:63]
	s_waitcnt lgkmcnt(3)
	v_mfma_f32_16x16x32_bf16 v[72:75], v[158:161], v[222:225], v[72:75]
	v_mfma_f32_16x16x32_bf16 v[76:79], v[162:165], v[222:225], v[76:79]
	s_waitcnt lgkmcnt(2)
	s_mov_b32 m0, s44
	v_mfma_f32_16x16x32_bf16 v[48:51], v[214:217], v[166:169], v[48:51]
	global_load_lds_dwordx4 v146, s[48:49]
	s_waitcnt lgkmcnt(1)
	v_mfma_f32_16x16x32_bf16 v[174:177], v[218:221], v[166:169], v[174:177]
	ds_read_b128 v[166:169], v6 offset:9216
	v_mfma_f32_16x16x32_bf16 v[64:67], v[214:217], v[178:181], v[64:67]
	v_mfma_f32_16x16x32_bf16 v[170:173], v[218:221], v[178:181], v[170:173]
	ds_read_b128 v[178:181], v6 offset:11264
	v_mfma_f32_16x16x32_bf16 v[80:83], v[214:217], v[222:225], v[80:83]
	v_mfma_f32_16x16x32_bf16 v[32:35], v[218:221], v[222:225], v[32:35]
	ds_read_b128 v[222:225], v6 offset:13312
	s_waitcnt lgkmcnt(3)
	v_mfma_f32_16x16x32_bf16 v[88:91], v[158:161], v[226:229], v[88:91]
	v_mfma_f32_16x16x32_bf16 v[92:95], v[162:165], v[226:229], v[92:95]
	v_mfma_f32_16x16x32_bf16 v[96:99], v[214:217], v[226:229], v[96:99]
	v_mfma_f32_16x16x32_bf16 v[36:39], v[218:221], v[226:229], v[36:39]
	ds_read_b128 v[226:229], v6 offset:15360
	s_waitcnt lgkmcnt(3)
	v_mfma_f32_16x16x32_bf16 v[104:107], v[158:161], v[166:169], v[104:107]
	v_mfma_f32_16x16x32_bf16 v[108:111], v[162:165], v[166:169], v[108:111]
	v_mfma_f32_16x16x32_bf16 v[112:115], v[214:217], v[166:169], v[112:115]
	v_mfma_f32_16x16x32_bf16 v[52:55], v[218:221], v[166:169], v[52:55]
	s_waitcnt lgkmcnt(2)
	v_mfma_f32_16x16x32_bf16 v[116:119], v[158:161], v[178:181], v[116:119]
	v_mfma_f32_16x16x32_bf16 v[120:123], v[162:165], v[178:181], v[120:123]
	v_mfma_f32_16x16x32_bf16 v[124:127], v[214:217], v[178:181], v[124:127]
	v_mfma_f32_16x16x32_bf16 v[68:71], v[218:221], v[178:181], v[68:71]
	s_waitcnt lgkmcnt(1)
	v_mfma_f32_16x16x32_bf16 v[128:131], v[158:161], v[222:225], v[128:131]
	v_mfma_f32_16x16x32_bf16 v[132:135], v[162:165], v[222:225], v[132:135]
	v_mfma_f32_16x16x32_bf16 v[136:139], v[214:217], v[222:225], v[136:139]
	v_mfma_f32_16x16x32_bf16 v[84:87], v[218:221], v[222:225], v[84:87]
	s_waitcnt lgkmcnt(0)
	v_mfma_f32_16x16x32_bf16 v[100:103], v[158:161], v[226:229], v[100:103]
	v_mfma_f32_16x16x32_bf16 v[140:143], v[162:165], v[226:229], v[140:143]
	v_mfma_f32_16x16x32_bf16 v[150:153], v[214:217], v[226:229], v[150:153]
	v_mfma_f32_16x16x32_bf16 v[154:157], v[218:221], v[226:229], v[154:157]
	s_add_u32 s46, s0, 0x2600
	s_addc_u32 s47, s1, 0
	s_add_u32 s48, s14, 0x2600
	s_waitcnt vmcnt(0)
	s_barrier
	s_addc_u32 s49, s15, 0
	ds_read_b128 v[158:161], v8
	ds_read_b128 v[162:165], v12
	ds_read_b128 v[166:169], v9
	ds_read_b128 v[178:181], v13
	ds_read_b128 v[214:217], v11
	ds_read_b128 v[218:221], v10
	ds_read_b128 v[222:225], v14
	ds_read_b128 v[226:229], v15
	s_waitcnt lgkmcnt(6)
	v_mfma_f32_16x16x32_bf16 v[40:43], v[158:161], v[162:165], v[40:43]
	s_waitcnt lgkmcnt(5)
	v_mfma_f32_16x16x32_bf16 v[44:47], v[166:169], v[162:165], v[44:47]
	s_waitcnt lgkmcnt(4)
	v_mfma_f32_16x16x32_bf16 v[56:59], v[158:161], v[178:181], v[56:59]
	s_mov_b32 m0, s27
	v_mfma_f32_16x16x32_bf16 v[60:63], v[166:169], v[178:181], v[60:63]
	global_load_lds_dwordx4 v0, s[46:47]
	s_waitcnt lgkmcnt(3)
	v_mfma_f32_16x16x32_bf16 v[48:51], v[214:217], v[162:165], v[48:51]
	v_mfma_f32_16x16x32_bf16 v[64:67], v[214:217], v[178:181], v[64:67]
	s_waitcnt lgkmcnt(2)
	v_mfma_f32_16x16x32_bf16 v[174:177], v[218:221], v[162:165], v[174:177]
	ds_read_b128 v[162:165], v16
	v_mfma_f32_16x16x32_bf16 v[170:173], v[218:221], v[178:181], v[170:173]
	ds_read_b128 v[178:181], v17
	s_waitcnt lgkmcnt(3)
	s_mov_b32 m0, s28
	v_mfma_f32_16x16x32_bf16 v[72:75], v[158:161], v[222:225], v[72:75]
	global_load_lds_dwordx4 v0, s[48:49]
	v_mfma_f32_16x16x32_bf16 v[76:79], v[166:169], v[222:225], v[76:79]
	v_mfma_f32_16x16x32_bf16 v[80:83], v[214:217], v[222:225], v[80:83]
	v_mfma_f32_16x16x32_bf16 v[32:35], v[218:221], v[222:225], v[32:35]
	ds_read_b128 v[222:225], v18
	s_waitcnt lgkmcnt(3)
	v_mfma_f32_16x16x32_bf16 v[88:91], v[158:161], v[226:229], v[88:91]
	s_mov_b32 m0, s29
	v_mfma_f32_16x16x32_bf16 v[92:95], v[166:169], v[226:229], v[92:95]
	global_load_lds_dwordx4 v2, s[46:47]
	v_mfma_f32_16x16x32_bf16 v[96:99], v[214:217], v[226:229], v[96:99]
	v_mfma_f32_16x16x32_bf16 v[36:39], v[218:221], v[226:229], v[36:39]
	ds_read_b128 v[226:229], v19
	s_waitcnt lgkmcnt(3)
	v_mfma_f32_16x16x32_bf16 v[104:107], v[158:161], v[162:165], v[104:107]
	s_waitcnt lgkmcnt(2)
	v_mfma_f32_16x16x32_bf16 v[116:119], v[158:161], v[178:181], v[116:119]
	s_waitcnt lgkmcnt(1)
	s_mov_b32 m0, s30
	v_mfma_f32_16x16x32_bf16 v[128:131], v[158:161], v[222:225], v[128:131]
	global_load_lds_dwordx4 v2, s[48:49]
	s_waitcnt lgkmcnt(0)
	v_mfma_f32_16x16x32_bf16 v[100:103], v[158:161], v[226:229], v[100:103]
	ds_read_b128 v[158:161], v20
	v_mfma_f32_16x16x32_bf16 v[108:111], v[166:169], v[162:165], v[108:111]
	v_mfma_f32_16x16x32_bf16 v[120:123], v[166:169], v[178:181], v[120:123]
	v_mfma_f32_16x16x32_bf16 v[132:135], v[166:169], v[222:225], v[132:135]
	s_mov_b32 m0, s31
	v_mfma_f32_16x16x32_bf16 v[140:143], v[166:169], v[226:229], v[140:143]
	global_load_lds_dwordx4 v4, s[46:47]
	ds_read_b128 v[166:169], v24
	v_mfma_f32_16x16x32_bf16 v[112:115], v[214:217], v[162:165], v[112:115]
	v_mfma_f32_16x16x32_bf16 v[52:55], v[218:221], v[162:165], v[52:55]
	ds_read_b128 v[162:165], v21
	v_mfma_f32_16x16x32_bf16 v[124:127], v[214:217], v[178:181], v[124:127]
	v_mfma_f32_16x16x32_bf16 v[68:71], v[218:221], v[178:181], v[68:71]
	ds_read_b128 v[178:181], v25
	s_mov_b32 m0, s34
	v_mfma_f32_16x16x32_bf16 v[136:139], v[214:217], v[222:225], v[136:139]
	global_load_lds_dwordx4 v4, s[48:49]
	v_mfma_f32_16x16x32_bf16 v[84:87], v[218:221], v[222:225], v[84:87]
	ds_read_b128 v[222:225], v26
	v_mfma_f32_16x16x32_bf16 v[150:153], v[214:217], v[226:229], v[150:153]
	ds_read_b128 v[214:217], v23
	v_mfma_f32_16x16x32_bf16 v[154:157], v[218:221], v[226:229], v[154:157]
	ds_read_b128 v[218:221], v22
	ds_read_b128 v[226:229], v27
	s_waitcnt lgkmcnt(6)
	v_mfma_f32_16x16x32_bf16 v[40:43], v[158:161], v[166:169], v[40:43]
	s_waitcnt lgkmcnt(5)
	s_mov_b32 m0, s35
	v_mfma_f32_16x16x32_bf16 v[44:47], v[162:165], v[166:169], v[44:47]
	global_load_lds_dwordx4 v146, s[46:47]
	s_waitcnt lgkmcnt(4)
	v_mfma_f32_16x16x32_bf16 v[56:59], v[158:161], v[178:181], v[56:59]
	v_mfma_f32_16x16x32_bf16 v[60:63], v[162:165], v[178:181], v[60:63]
	s_waitcnt lgkmcnt(3)
	v_mfma_f32_16x16x32_bf16 v[72:75], v[158:161], v[222:225], v[72:75]
	v_mfma_f32_16x16x32_bf16 v[76:79], v[162:165], v[222:225], v[76:79]
	s_waitcnt lgkmcnt(2)
	s_mov_b32 m0, s36
	v_mfma_f32_16x16x32_bf16 v[48:51], v[214:217], v[166:169], v[48:51]
	global_load_lds_dwordx4 v146, s[48:49]
	s_waitcnt lgkmcnt(1)
	v_mfma_f32_16x16x32_bf16 v[174:177], v[218:221], v[166:169], v[174:177]
	ds_read_b128 v[166:169], v28
	v_mfma_f32_16x16x32_bf16 v[64:67], v[214:217], v[178:181], v[64:67]
	v_mfma_f32_16x16x32_bf16 v[170:173], v[218:221], v[178:181], v[170:173]
	ds_read_b128 v[178:181], v29
	v_mfma_f32_16x16x32_bf16 v[80:83], v[214:217], v[222:225], v[80:83]
	v_mfma_f32_16x16x32_bf16 v[32:35], v[218:221], v[222:225], v[32:35]
	ds_read_b128 v[222:225], v30
	s_waitcnt lgkmcnt(3)
	v_mfma_f32_16x16x32_bf16 v[88:91], v[158:161], v[226:229], v[88:91]
	v_mfma_f32_16x16x32_bf16 v[92:95], v[162:165], v[226:229], v[92:95]
	v_mfma_f32_16x16x32_bf16 v[96:99], v[214:217], v[226:229], v[96:99]
	v_mfma_f32_16x16x32_bf16 v[36:39], v[218:221], v[226:229], v[36:39]
	ds_read_b128 v[226:229], v31
	s_waitcnt lgkmcnt(3)
	v_mfma_f32_16x16x32_bf16 v[104:107], v[158:161], v[166:169], v[104:107]
	v_mfma_f32_16x16x32_bf16 v[108:111], v[162:165], v[166:169], v[108:111]
	v_mfma_f32_16x16x32_bf16 v[112:115], v[214:217], v[166:169], v[112:115]
	v_mfma_f32_16x16x32_bf16 v[52:55], v[218:221], v[166:169], v[52:55]
	s_waitcnt lgkmcnt(2)
	v_mfma_f32_16x16x32_bf16 v[116:119], v[158:161], v[178:181], v[116:119]
	v_mfma_f32_16x16x32_bf16 v[120:123], v[162:165], v[178:181], v[120:123]
	v_mfma_f32_16x16x32_bf16 v[124:127], v[214:217], v[178:181], v[124:127]
	v_mfma_f32_16x16x32_bf16 v[68:71], v[218:221], v[178:181], v[68:71]
	s_waitcnt lgkmcnt(1)
	v_mfma_f32_16x16x32_bf16 v[128:131], v[158:161], v[222:225], v[128:131]
	v_mfma_f32_16x16x32_bf16 v[132:135], v[162:165], v[222:225], v[132:135]
	v_mfma_f32_16x16x32_bf16 v[136:139], v[214:217], v[222:225], v[136:139]
	v_mfma_f32_16x16x32_bf16 v[84:87], v[218:221], v[222:225], v[84:87]
	s_waitcnt lgkmcnt(0)
	v_mfma_f32_16x16x32_bf16 v[100:103], v[158:161], v[226:229], v[100:103]
	v_mfma_f32_16x16x32_bf16 v[140:143], v[162:165], v[226:229], v[140:143]
	v_mfma_f32_16x16x32_bf16 v[150:153], v[214:217], v[226:229], v[150:153]
	v_mfma_f32_16x16x32_bf16 v[154:157], v[218:221], v[226:229], v[154:157]
	s_add_u32 s46, s0, 0x2680
	s_addc_u32 s47, s1, 0
	s_add_u32 s48, s14, 0x2680
	s_waitcnt vmcnt(0)
	s_barrier
	s_addc_u32 s49, s15, 0
	ds_read_b128 v[158:161], v7 offset:32768
	ds_read_b128 v[162:165], v6
	ds_read_b128 v[166:169], v7 offset:34816
	ds_read_b128 v[178:181], v6 offset:2048
	ds_read_b128 v[214:217], v7 offset:36864
	ds_read_b128 v[218:221], v7 offset:38912
	ds_read_b128 v[222:225], v6 offset:4096
	ds_read_b128 v[226:229], v6 offset:6144
	s_waitcnt lgkmcnt(6)
	v_mfma_f32_16x16x32_bf16 v[40:43], v[158:161], v[162:165], v[40:43]
	s_waitcnt lgkmcnt(5)
	v_mfma_f32_16x16x32_bf16 v[44:47], v[166:169], v[162:165], v[44:47]
	s_waitcnt lgkmcnt(4)
	v_mfma_f32_16x16x32_bf16 v[56:59], v[158:161], v[178:181], v[56:59]
	s_mov_b32 m0, s38
	v_mfma_f32_16x16x32_bf16 v[60:63], v[166:169], v[178:181], v[60:63]
	global_load_lds_dwordx4 v0, s[46:47]
	s_waitcnt lgkmcnt(3)
	v_mfma_f32_16x16x32_bf16 v[48:51], v[214:217], v[162:165], v[48:51]
	v_mfma_f32_16x16x32_bf16 v[64:67], v[214:217], v[178:181], v[64:67]
	s_waitcnt lgkmcnt(2)
	v_mfma_f32_16x16x32_bf16 v[174:177], v[218:221], v[162:165], v[174:177]
	ds_read_b128 v[162:165], v6 offset:8192
	v_mfma_f32_16x16x32_bf16 v[170:173], v[218:221], v[178:181], v[170:173]
	ds_read_b128 v[178:181], v6 offset:10240
	s_waitcnt lgkmcnt(3)
	s_mov_b32 m0, s37
	v_mfma_f32_16x16x32_bf16 v[72:75], v[158:161], v[222:225], v[72:75]
	global_load_lds_dwordx4 v0, s[48:49]
	v_mfma_f32_16x16x32_bf16 v[76:79], v[166:169], v[222:225], v[76:79]
	v_mfma_f32_16x16x32_bf16 v[80:83], v[214:217], v[222:225], v[80:83]
	v_mfma_f32_16x16x32_bf16 v[32:35], v[218:221], v[222:225], v[32:35]
	ds_read_b128 v[222:225], v6 offset:12288
	s_waitcnt lgkmcnt(3)
	v_mfma_f32_16x16x32_bf16 v[88:91], v[158:161], v[226:229], v[88:91]
	s_mov_b32 m0, s39
	v_mfma_f32_16x16x32_bf16 v[92:95], v[166:169], v[226:229], v[92:95]
	global_load_lds_dwordx4 v2, s[46:47]
	v_mfma_f32_16x16x32_bf16 v[96:99], v[214:217], v[226:229], v[96:99]
	v_mfma_f32_16x16x32_bf16 v[36:39], v[218:221], v[226:229], v[36:39]
	ds_read_b128 v[226:229], v6 offset:14336
	s_waitcnt lgkmcnt(3)
	v_mfma_f32_16x16x32_bf16 v[104:107], v[158:161], v[162:165], v[104:107]
	s_waitcnt lgkmcnt(2)
	v_mfma_f32_16x16x32_bf16 v[116:119], v[158:161], v[178:181], v[116:119]
	s_waitcnt lgkmcnt(1)
	s_mov_b32 m0, s40
	v_mfma_f32_16x16x32_bf16 v[128:131], v[158:161], v[222:225], v[128:131]
	global_load_lds_dwordx4 v2, s[48:49]
	s_waitcnt lgkmcnt(0)
	v_mfma_f32_16x16x32_bf16 v[100:103], v[158:161], v[226:229], v[100:103]
	ds_read_b128 v[158:161], v7 offset:33792
	v_mfma_f32_16x16x32_bf16 v[108:111], v[166:169], v[162:165], v[108:111]
	v_mfma_f32_16x16x32_bf16 v[120:123], v[166:169], v[178:181], v[120:123]
	v_mfma_f32_16x16x32_bf16 v[132:135], v[166:169], v[222:225], v[132:135]
	s_mov_b32 m0, s41
	v_mfma_f32_16x16x32_bf16 v[140:143], v[166:169], v[226:229], v[140:143]
	global_load_lds_dwordx4 v4, s[46:47]
	ds_read_b128 v[166:169], v6 offset:1024
	v_mfma_f32_16x16x32_bf16 v[112:115], v[214:217], v[162:165], v[112:115]
	v_mfma_f32_16x16x32_bf16 v[52:55], v[218:221], v[162:165], v[52:55]
	ds_read_b128 v[162:165], v7 offset:35840
	v_mfma_f32_16x16x32_bf16 v[124:127], v[214:217], v[178:181], v[124:127]
	v_mfma_f32_16x16x32_bf16 v[68:71], v[218:221], v[178:181], v[68:71]
	ds_read_b128 v[178:181], v6 offset:3072
	s_mov_b32 m0, s42
	v_mfma_f32_16x16x32_bf16 v[136:139], v[214:217], v[222:225], v[136:139]
	global_load_lds_dwordx4 v4, s[48:49]
	v_mfma_f32_16x16x32_bf16 v[84:87], v[218:221], v[222:225], v[84:87]
	ds_read_b128 v[222:225], v6 offset:5120
	v_mfma_f32_16x16x32_bf16 v[150:153], v[214:217], v[226:229], v[150:153]
	ds_read_b128 v[214:217], v7 offset:37888
	v_mfma_f32_16x16x32_bf16 v[154:157], v[218:221], v[226:229], v[154:157]
	ds_read_b128 v[218:221], v7 offset:39936
	ds_read_b128 v[226:229], v6 offset:7168
	s_waitcnt lgkmcnt(6)
	v_mfma_f32_16x16x32_bf16 v[40:43], v[158:161], v[166:169], v[40:43]
	s_waitcnt lgkmcnt(5)
	s_mov_b32 m0, s43
	v_mfma_f32_16x16x32_bf16 v[44:47], v[162:165], v[166:169], v[44:47]
	global_load_lds_dwordx4 v146, s[46:47]
	s_waitcnt lgkmcnt(4)
	v_mfma_f32_16x16x32_bf16 v[56:59], v[158:161], v[178:181], v[56:59]
	v_mfma_f32_16x16x32_bf16 v[60:63], v[162:165], v[178:181], v[60:63]
	s_waitcnt lgkmcnt(3)
	v_mfma_f32_16x16x32_bf16 v[72:75], v[158:161], v[222:225], v[72:75]
	v_mfma_f32_16x16x32_bf16 v[76:79], v[162:165], v[222:225], v[76:79]
	s_waitcnt lgkmcnt(2)
	s_mov_b32 m0, s44
	v_mfma_f32_16x16x32_bf16 v[48:51], v[214:217], v[166:169], v[48:51]
	global_load_lds_dwordx4 v146, s[48:49]
	s_waitcnt lgkmcnt(1)
	v_mfma_f32_16x16x32_bf16 v[174:177], v[218:221], v[166:169], v[174:177]
	ds_read_b128 v[166:169], v6 offset:9216
	v_mfma_f32_16x16x32_bf16 v[64:67], v[214:217], v[178:181], v[64:67]
	v_mfma_f32_16x16x32_bf16 v[170:173], v[218:221], v[178:181], v[170:173]
	ds_read_b128 v[178:181], v6 offset:11264
	v_mfma_f32_16x16x32_bf16 v[80:83], v[214:217], v[222:225], v[80:83]
	v_mfma_f32_16x16x32_bf16 v[32:35], v[218:221], v[222:225], v[32:35]
	ds_read_b128 v[222:225], v6 offset:13312
	s_waitcnt lgkmcnt(3)
	v_mfma_f32_16x16x32_bf16 v[88:91], v[158:161], v[226:229], v[88:91]
	v_mfma_f32_16x16x32_bf16 v[92:95], v[162:165], v[226:229], v[92:95]
	v_mfma_f32_16x16x32_bf16 v[96:99], v[214:217], v[226:229], v[96:99]
	v_mfma_f32_16x16x32_bf16 v[36:39], v[218:221], v[226:229], v[36:39]
	ds_read_b128 v[226:229], v6 offset:15360
	s_waitcnt lgkmcnt(3)
	v_mfma_f32_16x16x32_bf16 v[104:107], v[158:161], v[166:169], v[104:107]
	v_mfma_f32_16x16x32_bf16 v[108:111], v[162:165], v[166:169], v[108:111]
	v_mfma_f32_16x16x32_bf16 v[112:115], v[214:217], v[166:169], v[112:115]
	v_mfma_f32_16x16x32_bf16 v[52:55], v[218:221], v[166:169], v[52:55]
	s_waitcnt lgkmcnt(2)
	v_mfma_f32_16x16x32_bf16 v[116:119], v[158:161], v[178:181], v[116:119]
	v_mfma_f32_16x16x32_bf16 v[120:123], v[162:165], v[178:181], v[120:123]
	v_mfma_f32_16x16x32_bf16 v[124:127], v[214:217], v[178:181], v[124:127]
	v_mfma_f32_16x16x32_bf16 v[68:71], v[218:221], v[178:181], v[68:71]
	s_waitcnt lgkmcnt(1)
	v_mfma_f32_16x16x32_bf16 v[128:131], v[158:161], v[222:225], v[128:131]
	v_mfma_f32_16x16x32_bf16 v[132:135], v[162:165], v[222:225], v[132:135]
	v_mfma_f32_16x16x32_bf16 v[136:139], v[214:217], v[222:225], v[136:139]
	v_mfma_f32_16x16x32_bf16 v[84:87], v[218:221], v[222:225], v[84:87]
	s_waitcnt lgkmcnt(0)
	v_mfma_f32_16x16x32_bf16 v[100:103], v[158:161], v[226:229], v[100:103]
	v_mfma_f32_16x16x32_bf16 v[140:143], v[162:165], v[226:229], v[140:143]
	v_mfma_f32_16x16x32_bf16 v[150:153], v[214:217], v[226:229], v[150:153]
	v_mfma_f32_16x16x32_bf16 v[154:157], v[218:221], v[226:229], v[154:157]
	s_add_u32 s46, s0, 0x2700
	s_addc_u32 s47, s1, 0
	s_add_u32 s48, s14, 0x2700
	s_waitcnt vmcnt(0)
	s_barrier
	s_addc_u32 s49, s15, 0
	ds_read_b128 v[158:161], v8
	ds_read_b128 v[162:165], v12
	ds_read_b128 v[166:169], v9
	ds_read_b128 v[178:181], v13
	ds_read_b128 v[214:217], v11
	ds_read_b128 v[218:221], v10
	ds_read_b128 v[222:225], v14
	ds_read_b128 v[226:229], v15
	s_waitcnt lgkmcnt(6)
	v_mfma_f32_16x16x32_bf16 v[40:43], v[158:161], v[162:165], v[40:43]
	s_waitcnt lgkmcnt(5)
	v_mfma_f32_16x16x32_bf16 v[44:47], v[166:169], v[162:165], v[44:47]
	s_waitcnt lgkmcnt(4)
	v_mfma_f32_16x16x32_bf16 v[56:59], v[158:161], v[178:181], v[56:59]
	s_mov_b32 m0, s27
	v_mfma_f32_16x16x32_bf16 v[60:63], v[166:169], v[178:181], v[60:63]
	global_load_lds_dwordx4 v0, s[46:47]
	s_waitcnt lgkmcnt(3)
	v_mfma_f32_16x16x32_bf16 v[48:51], v[214:217], v[162:165], v[48:51]
	v_mfma_f32_16x16x32_bf16 v[64:67], v[214:217], v[178:181], v[64:67]
	s_waitcnt lgkmcnt(2)
	v_mfma_f32_16x16x32_bf16 v[174:177], v[218:221], v[162:165], v[174:177]
	ds_read_b128 v[162:165], v16
	v_mfma_f32_16x16x32_bf16 v[170:173], v[218:221], v[178:181], v[170:173]
	ds_read_b128 v[178:181], v17
	s_waitcnt lgkmcnt(3)
	s_mov_b32 m0, s28
	v_mfma_f32_16x16x32_bf16 v[72:75], v[158:161], v[222:225], v[72:75]
	global_load_lds_dwordx4 v0, s[48:49]
	v_mfma_f32_16x16x32_bf16 v[76:79], v[166:169], v[222:225], v[76:79]
	v_mfma_f32_16x16x32_bf16 v[80:83], v[214:217], v[222:225], v[80:83]
	v_mfma_f32_16x16x32_bf16 v[32:35], v[218:221], v[222:225], v[32:35]
	ds_read_b128 v[222:225], v18
	s_waitcnt lgkmcnt(3)
	v_mfma_f32_16x16x32_bf16 v[88:91], v[158:161], v[226:229], v[88:91]
	s_mov_b32 m0, s29
	v_mfma_f32_16x16x32_bf16 v[92:95], v[166:169], v[226:229], v[92:95]
	global_load_lds_dwordx4 v2, s[46:47]
	v_mfma_f32_16x16x32_bf16 v[96:99], v[214:217], v[226:229], v[96:99]
	v_mfma_f32_16x16x32_bf16 v[36:39], v[218:221], v[226:229], v[36:39]
	ds_read_b128 v[226:229], v19
	s_waitcnt lgkmcnt(3)
	v_mfma_f32_16x16x32_bf16 v[104:107], v[158:161], v[162:165], v[104:107]
	s_waitcnt lgkmcnt(2)
	v_mfma_f32_16x16x32_bf16 v[116:119], v[158:161], v[178:181], v[116:119]
	s_waitcnt lgkmcnt(1)
	s_mov_b32 m0, s30
	v_mfma_f32_16x16x32_bf16 v[128:131], v[158:161], v[222:225], v[128:131]
	global_load_lds_dwordx4 v2, s[48:49]
	s_waitcnt lgkmcnt(0)
	v_mfma_f32_16x16x32_bf16 v[100:103], v[158:161], v[226:229], v[100:103]
	ds_read_b128 v[158:161], v20
	v_mfma_f32_16x16x32_bf16 v[108:111], v[166:169], v[162:165], v[108:111]
	v_mfma_f32_16x16x32_bf16 v[120:123], v[166:169], v[178:181], v[120:123]
	v_mfma_f32_16x16x32_bf16 v[132:135], v[166:169], v[222:225], v[132:135]
	s_mov_b32 m0, s31
	v_mfma_f32_16x16x32_bf16 v[140:143], v[166:169], v[226:229], v[140:143]
	global_load_lds_dwordx4 v4, s[46:47]
	ds_read_b128 v[166:169], v24
	v_mfma_f32_16x16x32_bf16 v[112:115], v[214:217], v[162:165], v[112:115]
	v_mfma_f32_16x16x32_bf16 v[52:55], v[218:221], v[162:165], v[52:55]
	ds_read_b128 v[162:165], v21
	v_mfma_f32_16x16x32_bf16 v[124:127], v[214:217], v[178:181], v[124:127]
	v_mfma_f32_16x16x32_bf16 v[68:71], v[218:221], v[178:181], v[68:71]
	ds_read_b128 v[178:181], v25
	s_mov_b32 m0, s34
	v_mfma_f32_16x16x32_bf16 v[136:139], v[214:217], v[222:225], v[136:139]
	global_load_lds_dwordx4 v4, s[48:49]
	v_mfma_f32_16x16x32_bf16 v[84:87], v[218:221], v[222:225], v[84:87]
	ds_read_b128 v[222:225], v26
	v_mfma_f32_16x16x32_bf16 v[150:153], v[214:217], v[226:229], v[150:153]
	ds_read_b128 v[214:217], v23
	v_mfma_f32_16x16x32_bf16 v[154:157], v[218:221], v[226:229], v[154:157]
	ds_read_b128 v[218:221], v22
	ds_read_b128 v[226:229], v27
	s_waitcnt lgkmcnt(6)
	v_mfma_f32_16x16x32_bf16 v[40:43], v[158:161], v[166:169], v[40:43]
	s_waitcnt lgkmcnt(5)
	s_mov_b32 m0, s35
	v_mfma_f32_16x16x32_bf16 v[44:47], v[162:165], v[166:169], v[44:47]
	global_load_lds_dwordx4 v146, s[46:47]
	s_waitcnt lgkmcnt(4)
	v_mfma_f32_16x16x32_bf16 v[56:59], v[158:161], v[178:181], v[56:59]
	v_mfma_f32_16x16x32_bf16 v[60:63], v[162:165], v[178:181], v[60:63]
	s_waitcnt lgkmcnt(3)
	v_mfma_f32_16x16x32_bf16 v[72:75], v[158:161], v[222:225], v[72:75]
	v_mfma_f32_16x16x32_bf16 v[76:79], v[162:165], v[222:225], v[76:79]
	s_waitcnt lgkmcnt(2)
	s_mov_b32 m0, s36
	v_mfma_f32_16x16x32_bf16 v[48:51], v[214:217], v[166:169], v[48:51]
	global_load_lds_dwordx4 v146, s[48:49]
	s_waitcnt lgkmcnt(1)
	v_mfma_f32_16x16x32_bf16 v[174:177], v[218:221], v[166:169], v[174:177]
	ds_read_b128 v[166:169], v28
	v_mfma_f32_16x16x32_bf16 v[64:67], v[214:217], v[178:181], v[64:67]
	v_mfma_f32_16x16x32_bf16 v[170:173], v[218:221], v[178:181], v[170:173]
	ds_read_b128 v[178:181], v29
	v_mfma_f32_16x16x32_bf16 v[80:83], v[214:217], v[222:225], v[80:83]
	v_mfma_f32_16x16x32_bf16 v[32:35], v[218:221], v[222:225], v[32:35]
	ds_read_b128 v[222:225], v30
	s_waitcnt lgkmcnt(3)
	v_mfma_f32_16x16x32_bf16 v[88:91], v[158:161], v[226:229], v[88:91]
	v_mfma_f32_16x16x32_bf16 v[92:95], v[162:165], v[226:229], v[92:95]
	v_mfma_f32_16x16x32_bf16 v[96:99], v[214:217], v[226:229], v[96:99]
	v_mfma_f32_16x16x32_bf16 v[36:39], v[218:221], v[226:229], v[36:39]
	ds_read_b128 v[226:229], v31
	s_waitcnt lgkmcnt(3)
	v_mfma_f32_16x16x32_bf16 v[104:107], v[158:161], v[166:169], v[104:107]
	v_mfma_f32_16x16x32_bf16 v[108:111], v[162:165], v[166:169], v[108:111]
	v_mfma_f32_16x16x32_bf16 v[112:115], v[214:217], v[166:169], v[112:115]
	v_mfma_f32_16x16x32_bf16 v[52:55], v[218:221], v[166:169], v[52:55]
	s_waitcnt lgkmcnt(2)
	v_mfma_f32_16x16x32_bf16 v[116:119], v[158:161], v[178:181], v[116:119]
	v_mfma_f32_16x16x32_bf16 v[120:123], v[162:165], v[178:181], v[120:123]
	v_mfma_f32_16x16x32_bf16 v[124:127], v[214:217], v[178:181], v[124:127]
	v_mfma_f32_16x16x32_bf16 v[68:71], v[218:221], v[178:181], v[68:71]
	s_waitcnt lgkmcnt(1)
	v_mfma_f32_16x16x32_bf16 v[128:131], v[158:161], v[222:225], v[128:131]
	v_mfma_f32_16x16x32_bf16 v[132:135], v[162:165], v[222:225], v[132:135]
	v_mfma_f32_16x16x32_bf16 v[136:139], v[214:217], v[222:225], v[136:139]
	v_mfma_f32_16x16x32_bf16 v[84:87], v[218:221], v[222:225], v[84:87]
	s_waitcnt lgkmcnt(0)
	v_mfma_f32_16x16x32_bf16 v[100:103], v[158:161], v[226:229], v[100:103]
	v_mfma_f32_16x16x32_bf16 v[140:143], v[162:165], v[226:229], v[140:143]
	v_mfma_f32_16x16x32_bf16 v[150:153], v[214:217], v[226:229], v[150:153]
	v_mfma_f32_16x16x32_bf16 v[154:157], v[218:221], v[226:229], v[154:157]
	s_add_u32 s46, s0, 0x2780
	s_addc_u32 s47, s1, 0
	s_add_u32 s48, s14, 0x2780
	s_waitcnt vmcnt(0)
	s_barrier
	s_addc_u32 s49, s15, 0
	ds_read_b128 v[158:161], v7 offset:32768
	ds_read_b128 v[162:165], v6
	ds_read_b128 v[166:169], v7 offset:34816
	ds_read_b128 v[178:181], v6 offset:2048
	ds_read_b128 v[214:217], v7 offset:36864
	ds_read_b128 v[218:221], v7 offset:38912
	ds_read_b128 v[222:225], v6 offset:4096
	ds_read_b128 v[226:229], v6 offset:6144
	s_waitcnt lgkmcnt(6)
	v_mfma_f32_16x16x32_bf16 v[40:43], v[158:161], v[162:165], v[40:43]
	s_waitcnt lgkmcnt(5)
	v_mfma_f32_16x16x32_bf16 v[44:47], v[166:169], v[162:165], v[44:47]
	s_waitcnt lgkmcnt(4)
	v_mfma_f32_16x16x32_bf16 v[56:59], v[158:161], v[178:181], v[56:59]
	s_mov_b32 m0, s38
	v_mfma_f32_16x16x32_bf16 v[60:63], v[166:169], v[178:181], v[60:63]
	global_load_lds_dwordx4 v0, s[46:47]
	s_waitcnt lgkmcnt(3)
	v_mfma_f32_16x16x32_bf16 v[48:51], v[214:217], v[162:165], v[48:51]
	v_mfma_f32_16x16x32_bf16 v[64:67], v[214:217], v[178:181], v[64:67]
	s_waitcnt lgkmcnt(2)
	v_mfma_f32_16x16x32_bf16 v[174:177], v[218:221], v[162:165], v[174:177]
	ds_read_b128 v[162:165], v6 offset:8192
	v_mfma_f32_16x16x32_bf16 v[170:173], v[218:221], v[178:181], v[170:173]
	ds_read_b128 v[178:181], v6 offset:10240
	s_waitcnt lgkmcnt(3)
	s_mov_b32 m0, s37
	v_mfma_f32_16x16x32_bf16 v[72:75], v[158:161], v[222:225], v[72:75]
	global_load_lds_dwordx4 v0, s[48:49]
	v_mfma_f32_16x16x32_bf16 v[76:79], v[166:169], v[222:225], v[76:79]
	v_mfma_f32_16x16x32_bf16 v[80:83], v[214:217], v[222:225], v[80:83]
	v_mfma_f32_16x16x32_bf16 v[32:35], v[218:221], v[222:225], v[32:35]
	ds_read_b128 v[222:225], v6 offset:12288
	s_waitcnt lgkmcnt(3)
	v_mfma_f32_16x16x32_bf16 v[88:91], v[158:161], v[226:229], v[88:91]
	s_mov_b32 m0, s39
	v_mfma_f32_16x16x32_bf16 v[92:95], v[166:169], v[226:229], v[92:95]
	global_load_lds_dwordx4 v2, s[46:47]
	v_mfma_f32_16x16x32_bf16 v[96:99], v[214:217], v[226:229], v[96:99]
	v_mfma_f32_16x16x32_bf16 v[36:39], v[218:221], v[226:229], v[36:39]
	ds_read_b128 v[226:229], v6 offset:14336
	s_waitcnt lgkmcnt(3)
	v_mfma_f32_16x16x32_bf16 v[104:107], v[158:161], v[162:165], v[104:107]
	s_waitcnt lgkmcnt(2)
	v_mfma_f32_16x16x32_bf16 v[116:119], v[158:161], v[178:181], v[116:119]
	s_waitcnt lgkmcnt(1)
	s_mov_b32 m0, s40
	v_mfma_f32_16x16x32_bf16 v[128:131], v[158:161], v[222:225], v[128:131]
	global_load_lds_dwordx4 v2, s[48:49]
	s_waitcnt lgkmcnt(0)
	v_mfma_f32_16x16x32_bf16 v[100:103], v[158:161], v[226:229], v[100:103]
	ds_read_b128 v[158:161], v7 offset:33792
	v_mfma_f32_16x16x32_bf16 v[108:111], v[166:169], v[162:165], v[108:111]
	v_mfma_f32_16x16x32_bf16 v[120:123], v[166:169], v[178:181], v[120:123]
	v_mfma_f32_16x16x32_bf16 v[132:135], v[166:169], v[222:225], v[132:135]
	s_mov_b32 m0, s41
	v_mfma_f32_16x16x32_bf16 v[140:143], v[166:169], v[226:229], v[140:143]
	global_load_lds_dwordx4 v4, s[46:47]
	ds_read_b128 v[166:169], v6 offset:1024
	v_mfma_f32_16x16x32_bf16 v[112:115], v[214:217], v[162:165], v[112:115]
	v_mfma_f32_16x16x32_bf16 v[52:55], v[218:221], v[162:165], v[52:55]
	ds_read_b128 v[162:165], v7 offset:35840
	v_mfma_f32_16x16x32_bf16 v[124:127], v[214:217], v[178:181], v[124:127]
	v_mfma_f32_16x16x32_bf16 v[68:71], v[218:221], v[178:181], v[68:71]
	ds_read_b128 v[178:181], v6 offset:3072
	s_mov_b32 m0, s42
	v_mfma_f32_16x16x32_bf16 v[136:139], v[214:217], v[222:225], v[136:139]
	global_load_lds_dwordx4 v4, s[48:49]
	v_mfma_f32_16x16x32_bf16 v[84:87], v[218:221], v[222:225], v[84:87]
	ds_read_b128 v[222:225], v6 offset:5120
	v_mfma_f32_16x16x32_bf16 v[150:153], v[214:217], v[226:229], v[150:153]
	ds_read_b128 v[214:217], v7 offset:37888
	v_mfma_f32_16x16x32_bf16 v[154:157], v[218:221], v[226:229], v[154:157]
	ds_read_b128 v[218:221], v7 offset:39936
	ds_read_b128 v[226:229], v6 offset:7168
	s_waitcnt lgkmcnt(6)
	v_mfma_f32_16x16x32_bf16 v[40:43], v[158:161], v[166:169], v[40:43]
	s_waitcnt lgkmcnt(5)
	s_mov_b32 m0, s43
	v_mfma_f32_16x16x32_bf16 v[44:47], v[162:165], v[166:169], v[44:47]
	global_load_lds_dwordx4 v146, s[46:47]
	s_waitcnt lgkmcnt(4)
	v_mfma_f32_16x16x32_bf16 v[56:59], v[158:161], v[178:181], v[56:59]
	v_mfma_f32_16x16x32_bf16 v[60:63], v[162:165], v[178:181], v[60:63]
	s_waitcnt lgkmcnt(3)
	v_mfma_f32_16x16x32_bf16 v[72:75], v[158:161], v[222:225], v[72:75]
	v_mfma_f32_16x16x32_bf16 v[76:79], v[162:165], v[222:225], v[76:79]
	s_waitcnt lgkmcnt(2)
	s_mov_b32 m0, s44
	v_mfma_f32_16x16x32_bf16 v[48:51], v[214:217], v[166:169], v[48:51]
	global_load_lds_dwordx4 v146, s[48:49]
	s_waitcnt lgkmcnt(1)
	v_mfma_f32_16x16x32_bf16 v[174:177], v[218:221], v[166:169], v[174:177]
	ds_read_b128 v[166:169], v6 offset:9216
	v_mfma_f32_16x16x32_bf16 v[64:67], v[214:217], v[178:181], v[64:67]
	v_mfma_f32_16x16x32_bf16 v[170:173], v[218:221], v[178:181], v[170:173]
	ds_read_b128 v[178:181], v6 offset:11264
	v_mfma_f32_16x16x32_bf16 v[80:83], v[214:217], v[222:225], v[80:83]
	v_mfma_f32_16x16x32_bf16 v[32:35], v[218:221], v[222:225], v[32:35]
	ds_read_b128 v[222:225], v6 offset:13312
	s_waitcnt lgkmcnt(3)
	v_mfma_f32_16x16x32_bf16 v[88:91], v[158:161], v[226:229], v[88:91]
	v_mfma_f32_16x16x32_bf16 v[92:95], v[162:165], v[226:229], v[92:95]
	v_mfma_f32_16x16x32_bf16 v[96:99], v[214:217], v[226:229], v[96:99]
	v_mfma_f32_16x16x32_bf16 v[36:39], v[218:221], v[226:229], v[36:39]
	ds_read_b128 v[226:229], v6 offset:15360
	s_waitcnt lgkmcnt(3)
	v_mfma_f32_16x16x32_bf16 v[104:107], v[158:161], v[166:169], v[104:107]
	v_mfma_f32_16x16x32_bf16 v[108:111], v[162:165], v[166:169], v[108:111]
	v_mfma_f32_16x16x32_bf16 v[112:115], v[214:217], v[166:169], v[112:115]
	v_mfma_f32_16x16x32_bf16 v[52:55], v[218:221], v[166:169], v[52:55]
	s_waitcnt lgkmcnt(2)
	v_mfma_f32_16x16x32_bf16 v[116:119], v[158:161], v[178:181], v[116:119]
	v_mfma_f32_16x16x32_bf16 v[120:123], v[162:165], v[178:181], v[120:123]
	v_mfma_f32_16x16x32_bf16 v[124:127], v[214:217], v[178:181], v[124:127]
	v_mfma_f32_16x16x32_bf16 v[68:71], v[218:221], v[178:181], v[68:71]
	s_waitcnt lgkmcnt(1)
	v_mfma_f32_16x16x32_bf16 v[128:131], v[158:161], v[222:225], v[128:131]
	v_mfma_f32_16x16x32_bf16 v[132:135], v[162:165], v[222:225], v[132:135]
	v_mfma_f32_16x16x32_bf16 v[136:139], v[214:217], v[222:225], v[136:139]
	v_mfma_f32_16x16x32_bf16 v[84:87], v[218:221], v[222:225], v[84:87]
	s_waitcnt lgkmcnt(0)
	v_mfma_f32_16x16x32_bf16 v[100:103], v[158:161], v[226:229], v[100:103]
	v_mfma_f32_16x16x32_bf16 v[140:143], v[162:165], v[226:229], v[140:143]
	v_mfma_f32_16x16x32_bf16 v[150:153], v[214:217], v[226:229], v[150:153]
	v_mfma_f32_16x16x32_bf16 v[154:157], v[218:221], v[226:229], v[154:157]
	s_add_u32 s46, s0, 0x2800
	s_addc_u32 s47, s1, 0
	s_add_u32 s48, s14, 0x2800
	s_waitcnt vmcnt(0)
	s_barrier
	s_addc_u32 s49, s15, 0
	ds_read_b128 v[158:161], v8
	ds_read_b128 v[162:165], v12
	ds_read_b128 v[166:169], v9
	ds_read_b128 v[178:181], v13
	ds_read_b128 v[214:217], v11
	ds_read_b128 v[218:221], v10
	ds_read_b128 v[222:225], v14
	ds_read_b128 v[226:229], v15
	s_waitcnt lgkmcnt(6)
	v_mfma_f32_16x16x32_bf16 v[40:43], v[158:161], v[162:165], v[40:43]
	s_waitcnt lgkmcnt(5)
	v_mfma_f32_16x16x32_bf16 v[44:47], v[166:169], v[162:165], v[44:47]
	s_waitcnt lgkmcnt(4)
	v_mfma_f32_16x16x32_bf16 v[56:59], v[158:161], v[178:181], v[56:59]
	s_mov_b32 m0, s27
	v_mfma_f32_16x16x32_bf16 v[60:63], v[166:169], v[178:181], v[60:63]
	global_load_lds_dwordx4 v0, s[46:47]
	s_waitcnt lgkmcnt(3)
	v_mfma_f32_16x16x32_bf16 v[48:51], v[214:217], v[162:165], v[48:51]
	v_mfma_f32_16x16x32_bf16 v[64:67], v[214:217], v[178:181], v[64:67]
	s_waitcnt lgkmcnt(2)
	v_mfma_f32_16x16x32_bf16 v[174:177], v[218:221], v[162:165], v[174:177]
	ds_read_b128 v[162:165], v16
	v_mfma_f32_16x16x32_bf16 v[170:173], v[218:221], v[178:181], v[170:173]
	ds_read_b128 v[178:181], v17
	s_waitcnt lgkmcnt(3)
	s_mov_b32 m0, s28
	v_mfma_f32_16x16x32_bf16 v[72:75], v[158:161], v[222:225], v[72:75]
	global_load_lds_dwordx4 v0, s[48:49]
	v_mfma_f32_16x16x32_bf16 v[76:79], v[166:169], v[222:225], v[76:79]
	v_mfma_f32_16x16x32_bf16 v[80:83], v[214:217], v[222:225], v[80:83]
	v_mfma_f32_16x16x32_bf16 v[32:35], v[218:221], v[222:225], v[32:35]
	ds_read_b128 v[222:225], v18
	s_waitcnt lgkmcnt(3)
	v_mfma_f32_16x16x32_bf16 v[88:91], v[158:161], v[226:229], v[88:91]
	s_mov_b32 m0, s29
	v_mfma_f32_16x16x32_bf16 v[92:95], v[166:169], v[226:229], v[92:95]
	global_load_lds_dwordx4 v2, s[46:47]
	v_mfma_f32_16x16x32_bf16 v[96:99], v[214:217], v[226:229], v[96:99]
	v_mfma_f32_16x16x32_bf16 v[36:39], v[218:221], v[226:229], v[36:39]
	ds_read_b128 v[226:229], v19
	s_waitcnt lgkmcnt(3)
	v_mfma_f32_16x16x32_bf16 v[104:107], v[158:161], v[162:165], v[104:107]
	s_waitcnt lgkmcnt(2)
	v_mfma_f32_16x16x32_bf16 v[116:119], v[158:161], v[178:181], v[116:119]
	s_waitcnt lgkmcnt(1)
	s_mov_b32 m0, s30
	v_mfma_f32_16x16x32_bf16 v[128:131], v[158:161], v[222:225], v[128:131]
	global_load_lds_dwordx4 v2, s[48:49]
	s_waitcnt lgkmcnt(0)
	v_mfma_f32_16x16x32_bf16 v[100:103], v[158:161], v[226:229], v[100:103]
	ds_read_b128 v[158:161], v20
	v_mfma_f32_16x16x32_bf16 v[108:111], v[166:169], v[162:165], v[108:111]
	v_mfma_f32_16x16x32_bf16 v[120:123], v[166:169], v[178:181], v[120:123]
	v_mfma_f32_16x16x32_bf16 v[132:135], v[166:169], v[222:225], v[132:135]
	s_mov_b32 m0, s31
	v_mfma_f32_16x16x32_bf16 v[140:143], v[166:169], v[226:229], v[140:143]
	global_load_lds_dwordx4 v4, s[46:47]
	ds_read_b128 v[166:169], v24
	v_mfma_f32_16x16x32_bf16 v[112:115], v[214:217], v[162:165], v[112:115]
	v_mfma_f32_16x16x32_bf16 v[52:55], v[218:221], v[162:165], v[52:55]
	ds_read_b128 v[162:165], v21
	v_mfma_f32_16x16x32_bf16 v[124:127], v[214:217], v[178:181], v[124:127]
	v_mfma_f32_16x16x32_bf16 v[68:71], v[218:221], v[178:181], v[68:71]
	ds_read_b128 v[178:181], v25
	s_mov_b32 m0, s34
	v_mfma_f32_16x16x32_bf16 v[136:139], v[214:217], v[222:225], v[136:139]
	global_load_lds_dwordx4 v4, s[48:49]
	v_mfma_f32_16x16x32_bf16 v[84:87], v[218:221], v[222:225], v[84:87]
	ds_read_b128 v[222:225], v26
	v_mfma_f32_16x16x32_bf16 v[150:153], v[214:217], v[226:229], v[150:153]
	ds_read_b128 v[214:217], v23
	v_mfma_f32_16x16x32_bf16 v[154:157], v[218:221], v[226:229], v[154:157]
	ds_read_b128 v[218:221], v22
	ds_read_b128 v[226:229], v27
	s_waitcnt lgkmcnt(6)
	v_mfma_f32_16x16x32_bf16 v[40:43], v[158:161], v[166:169], v[40:43]
	s_waitcnt lgkmcnt(5)
	s_mov_b32 m0, s35
	v_mfma_f32_16x16x32_bf16 v[44:47], v[162:165], v[166:169], v[44:47]
	global_load_lds_dwordx4 v146, s[46:47]
	s_waitcnt lgkmcnt(4)
	v_mfma_f32_16x16x32_bf16 v[56:59], v[158:161], v[178:181], v[56:59]
	v_mfma_f32_16x16x32_bf16 v[60:63], v[162:165], v[178:181], v[60:63]
	s_waitcnt lgkmcnt(3)
	v_mfma_f32_16x16x32_bf16 v[72:75], v[158:161], v[222:225], v[72:75]
	v_mfma_f32_16x16x32_bf16 v[76:79], v[162:165], v[222:225], v[76:79]
	s_waitcnt lgkmcnt(2)
	s_mov_b32 m0, s36
	v_mfma_f32_16x16x32_bf16 v[48:51], v[214:217], v[166:169], v[48:51]
	global_load_lds_dwordx4 v146, s[48:49]
	s_waitcnt lgkmcnt(1)
	v_mfma_f32_16x16x32_bf16 v[174:177], v[218:221], v[166:169], v[174:177]
	ds_read_b128 v[166:169], v28
	v_mfma_f32_16x16x32_bf16 v[64:67], v[214:217], v[178:181], v[64:67]
	v_mfma_f32_16x16x32_bf16 v[170:173], v[218:221], v[178:181], v[170:173]
	ds_read_b128 v[178:181], v29
	v_mfma_f32_16x16x32_bf16 v[80:83], v[214:217], v[222:225], v[80:83]
	v_mfma_f32_16x16x32_bf16 v[32:35], v[218:221], v[222:225], v[32:35]
	ds_read_b128 v[222:225], v30
	s_waitcnt lgkmcnt(3)
	v_mfma_f32_16x16x32_bf16 v[88:91], v[158:161], v[226:229], v[88:91]
	v_mfma_f32_16x16x32_bf16 v[92:95], v[162:165], v[226:229], v[92:95]
	v_mfma_f32_16x16x32_bf16 v[96:99], v[214:217], v[226:229], v[96:99]
	v_mfma_f32_16x16x32_bf16 v[36:39], v[218:221], v[226:229], v[36:39]
	ds_read_b128 v[226:229], v31
	s_waitcnt lgkmcnt(3)
	v_mfma_f32_16x16x32_bf16 v[104:107], v[158:161], v[166:169], v[104:107]
	v_mfma_f32_16x16x32_bf16 v[108:111], v[162:165], v[166:169], v[108:111]
	v_mfma_f32_16x16x32_bf16 v[112:115], v[214:217], v[166:169], v[112:115]
	v_mfma_f32_16x16x32_bf16 v[52:55], v[218:221], v[166:169], v[52:55]
	s_waitcnt lgkmcnt(2)
	v_mfma_f32_16x16x32_bf16 v[116:119], v[158:161], v[178:181], v[116:119]
	v_mfma_f32_16x16x32_bf16 v[120:123], v[162:165], v[178:181], v[120:123]
	v_mfma_f32_16x16x32_bf16 v[124:127], v[214:217], v[178:181], v[124:127]
	v_mfma_f32_16x16x32_bf16 v[68:71], v[218:221], v[178:181], v[68:71]
	s_waitcnt lgkmcnt(1)
	v_mfma_f32_16x16x32_bf16 v[128:131], v[158:161], v[222:225], v[128:131]
	v_mfma_f32_16x16x32_bf16 v[132:135], v[162:165], v[222:225], v[132:135]
	v_mfma_f32_16x16x32_bf16 v[136:139], v[214:217], v[222:225], v[136:139]
	v_mfma_f32_16x16x32_bf16 v[84:87], v[218:221], v[222:225], v[84:87]
	s_waitcnt lgkmcnt(0)
	v_mfma_f32_16x16x32_bf16 v[100:103], v[158:161], v[226:229], v[100:103]
	v_mfma_f32_16x16x32_bf16 v[140:143], v[162:165], v[226:229], v[140:143]
	v_mfma_f32_16x16x32_bf16 v[150:153], v[214:217], v[226:229], v[150:153]
	v_mfma_f32_16x16x32_bf16 v[154:157], v[218:221], v[226:229], v[154:157]
	s_add_u32 s46, s0, 0x2880
	s_addc_u32 s47, s1, 0
	s_add_u32 s48, s14, 0x2880
	s_waitcnt vmcnt(0)
	s_barrier
	s_addc_u32 s49, s15, 0
	ds_read_b128 v[158:161], v7 offset:32768
	ds_read_b128 v[162:165], v6
	ds_read_b128 v[166:169], v7 offset:34816
	ds_read_b128 v[178:181], v6 offset:2048
	ds_read_b128 v[214:217], v7 offset:36864
	ds_read_b128 v[218:221], v7 offset:38912
	ds_read_b128 v[222:225], v6 offset:4096
	ds_read_b128 v[226:229], v6 offset:6144
	s_waitcnt lgkmcnt(6)
	v_mfma_f32_16x16x32_bf16 v[40:43], v[158:161], v[162:165], v[40:43]
	s_waitcnt lgkmcnt(5)
	v_mfma_f32_16x16x32_bf16 v[44:47], v[166:169], v[162:165], v[44:47]
	s_waitcnt lgkmcnt(4)
	v_mfma_f32_16x16x32_bf16 v[56:59], v[158:161], v[178:181], v[56:59]
	s_mov_b32 m0, s38
	v_mfma_f32_16x16x32_bf16 v[60:63], v[166:169], v[178:181], v[60:63]
	global_load_lds_dwordx4 v0, s[46:47]
	s_waitcnt lgkmcnt(3)
	v_mfma_f32_16x16x32_bf16 v[48:51], v[214:217], v[162:165], v[48:51]
	v_mfma_f32_16x16x32_bf16 v[64:67], v[214:217], v[178:181], v[64:67]
	s_waitcnt lgkmcnt(2)
	v_mfma_f32_16x16x32_bf16 v[174:177], v[218:221], v[162:165], v[174:177]
	ds_read_b128 v[162:165], v6 offset:8192
	v_mfma_f32_16x16x32_bf16 v[170:173], v[218:221], v[178:181], v[170:173]
	ds_read_b128 v[178:181], v6 offset:10240
	s_waitcnt lgkmcnt(3)
	s_mov_b32 m0, s37
	v_mfma_f32_16x16x32_bf16 v[72:75], v[158:161], v[222:225], v[72:75]
	global_load_lds_dwordx4 v0, s[48:49]
	v_mfma_f32_16x16x32_bf16 v[76:79], v[166:169], v[222:225], v[76:79]
	v_mfma_f32_16x16x32_bf16 v[80:83], v[214:217], v[222:225], v[80:83]
	v_mfma_f32_16x16x32_bf16 v[32:35], v[218:221], v[222:225], v[32:35]
	ds_read_b128 v[222:225], v6 offset:12288
	s_waitcnt lgkmcnt(3)
	v_mfma_f32_16x16x32_bf16 v[88:91], v[158:161], v[226:229], v[88:91]
	s_mov_b32 m0, s39
	v_mfma_f32_16x16x32_bf16 v[92:95], v[166:169], v[226:229], v[92:95]
	global_load_lds_dwordx4 v2, s[46:47]
	v_mfma_f32_16x16x32_bf16 v[96:99], v[214:217], v[226:229], v[96:99]
	v_mfma_f32_16x16x32_bf16 v[36:39], v[218:221], v[226:229], v[36:39]
	ds_read_b128 v[226:229], v6 offset:14336
	s_waitcnt lgkmcnt(3)
	v_mfma_f32_16x16x32_bf16 v[104:107], v[158:161], v[162:165], v[104:107]
	s_waitcnt lgkmcnt(2)
	v_mfma_f32_16x16x32_bf16 v[116:119], v[158:161], v[178:181], v[116:119]
	s_waitcnt lgkmcnt(1)
	s_mov_b32 m0, s40
	v_mfma_f32_16x16x32_bf16 v[128:131], v[158:161], v[222:225], v[128:131]
	global_load_lds_dwordx4 v2, s[48:49]
	s_waitcnt lgkmcnt(0)
	v_mfma_f32_16x16x32_bf16 v[100:103], v[158:161], v[226:229], v[100:103]
	ds_read_b128 v[158:161], v7 offset:33792
	v_mfma_f32_16x16x32_bf16 v[108:111], v[166:169], v[162:165], v[108:111]
	v_mfma_f32_16x16x32_bf16 v[120:123], v[166:169], v[178:181], v[120:123]
	v_mfma_f32_16x16x32_bf16 v[132:135], v[166:169], v[222:225], v[132:135]
	s_mov_b32 m0, s41
	v_mfma_f32_16x16x32_bf16 v[140:143], v[166:169], v[226:229], v[140:143]
	global_load_lds_dwordx4 v4, s[46:47]
	ds_read_b128 v[166:169], v6 offset:1024
	v_mfma_f32_16x16x32_bf16 v[112:115], v[214:217], v[162:165], v[112:115]
	v_mfma_f32_16x16x32_bf16 v[52:55], v[218:221], v[162:165], v[52:55]
	ds_read_b128 v[162:165], v7 offset:35840
	v_mfma_f32_16x16x32_bf16 v[124:127], v[214:217], v[178:181], v[124:127]
	v_mfma_f32_16x16x32_bf16 v[68:71], v[218:221], v[178:181], v[68:71]
	ds_read_b128 v[178:181], v6 offset:3072
	s_mov_b32 m0, s42
	v_mfma_f32_16x16x32_bf16 v[136:139], v[214:217], v[222:225], v[136:139]
	global_load_lds_dwordx4 v4, s[48:49]
	v_mfma_f32_16x16x32_bf16 v[84:87], v[218:221], v[222:225], v[84:87]
	ds_read_b128 v[222:225], v6 offset:5120
	v_mfma_f32_16x16x32_bf16 v[150:153], v[214:217], v[226:229], v[150:153]
	ds_read_b128 v[214:217], v7 offset:37888
	v_mfma_f32_16x16x32_bf16 v[154:157], v[218:221], v[226:229], v[154:157]
	ds_read_b128 v[218:221], v7 offset:39936
	ds_read_b128 v[226:229], v6 offset:7168
	s_waitcnt lgkmcnt(6)
	v_mfma_f32_16x16x32_bf16 v[40:43], v[158:161], v[166:169], v[40:43]
	s_waitcnt lgkmcnt(5)
	s_mov_b32 m0, s43
	v_mfma_f32_16x16x32_bf16 v[44:47], v[162:165], v[166:169], v[44:47]
	global_load_lds_dwordx4 v146, s[46:47]
	s_waitcnt lgkmcnt(4)
	v_mfma_f32_16x16x32_bf16 v[56:59], v[158:161], v[178:181], v[56:59]
	v_mfma_f32_16x16x32_bf16 v[60:63], v[162:165], v[178:181], v[60:63]
	s_waitcnt lgkmcnt(3)
	v_mfma_f32_16x16x32_bf16 v[72:75], v[158:161], v[222:225], v[72:75]
	v_mfma_f32_16x16x32_bf16 v[76:79], v[162:165], v[222:225], v[76:79]
	s_waitcnt lgkmcnt(2)
	s_mov_b32 m0, s44
	v_mfma_f32_16x16x32_bf16 v[48:51], v[214:217], v[166:169], v[48:51]
	global_load_lds_dwordx4 v146, s[48:49]
	s_waitcnt lgkmcnt(1)
	v_mfma_f32_16x16x32_bf16 v[174:177], v[218:221], v[166:169], v[174:177]
	ds_read_b128 v[166:169], v6 offset:9216
	v_mfma_f32_16x16x32_bf16 v[64:67], v[214:217], v[178:181], v[64:67]
	v_mfma_f32_16x16x32_bf16 v[170:173], v[218:221], v[178:181], v[170:173]
	ds_read_b128 v[178:181], v6 offset:11264
	v_mfma_f32_16x16x32_bf16 v[80:83], v[214:217], v[222:225], v[80:83]
	v_mfma_f32_16x16x32_bf16 v[32:35], v[218:221], v[222:225], v[32:35]
	ds_read_b128 v[222:225], v6 offset:13312
	s_waitcnt lgkmcnt(3)
	v_mfma_f32_16x16x32_bf16 v[88:91], v[158:161], v[226:229], v[88:91]
	v_mfma_f32_16x16x32_bf16 v[92:95], v[162:165], v[226:229], v[92:95]
	v_mfma_f32_16x16x32_bf16 v[96:99], v[214:217], v[226:229], v[96:99]
	v_mfma_f32_16x16x32_bf16 v[36:39], v[218:221], v[226:229], v[36:39]
	ds_read_b128 v[226:229], v6 offset:15360
	s_waitcnt lgkmcnt(3)
	v_mfma_f32_16x16x32_bf16 v[104:107], v[158:161], v[166:169], v[104:107]
	v_mfma_f32_16x16x32_bf16 v[108:111], v[162:165], v[166:169], v[108:111]
	v_mfma_f32_16x16x32_bf16 v[112:115], v[214:217], v[166:169], v[112:115]
	v_mfma_f32_16x16x32_bf16 v[52:55], v[218:221], v[166:169], v[52:55]
	s_waitcnt lgkmcnt(2)
	v_mfma_f32_16x16x32_bf16 v[116:119], v[158:161], v[178:181], v[116:119]
	v_mfma_f32_16x16x32_bf16 v[120:123], v[162:165], v[178:181], v[120:123]
	v_mfma_f32_16x16x32_bf16 v[124:127], v[214:217], v[178:181], v[124:127]
	v_mfma_f32_16x16x32_bf16 v[68:71], v[218:221], v[178:181], v[68:71]
	s_waitcnt lgkmcnt(1)
	v_mfma_f32_16x16x32_bf16 v[128:131], v[158:161], v[222:225], v[128:131]
	v_mfma_f32_16x16x32_bf16 v[132:135], v[162:165], v[222:225], v[132:135]
	v_mfma_f32_16x16x32_bf16 v[136:139], v[214:217], v[222:225], v[136:139]
	v_mfma_f32_16x16x32_bf16 v[84:87], v[218:221], v[222:225], v[84:87]
	s_waitcnt lgkmcnt(0)
	v_mfma_f32_16x16x32_bf16 v[100:103], v[158:161], v[226:229], v[100:103]
	v_mfma_f32_16x16x32_bf16 v[140:143], v[162:165], v[226:229], v[140:143]
	v_mfma_f32_16x16x32_bf16 v[150:153], v[214:217], v[226:229], v[150:153]
	v_mfma_f32_16x16x32_bf16 v[154:157], v[218:221], v[226:229], v[154:157]
	s_add_u32 s46, s0, 0x2900
	s_addc_u32 s47, s1, 0
	s_add_u32 s48, s14, 0x2900
	s_waitcnt vmcnt(0)
	s_barrier
	s_addc_u32 s49, s15, 0
	ds_read_b128 v[158:161], v8
	ds_read_b128 v[162:165], v12
	ds_read_b128 v[166:169], v9
	ds_read_b128 v[178:181], v13
	ds_read_b128 v[214:217], v11
	ds_read_b128 v[218:221], v10
	ds_read_b128 v[222:225], v14
	ds_read_b128 v[226:229], v15
	s_waitcnt lgkmcnt(6)
	v_mfma_f32_16x16x32_bf16 v[40:43], v[158:161], v[162:165], v[40:43]
	s_waitcnt lgkmcnt(5)
	v_mfma_f32_16x16x32_bf16 v[44:47], v[166:169], v[162:165], v[44:47]
	s_waitcnt lgkmcnt(4)
	v_mfma_f32_16x16x32_bf16 v[56:59], v[158:161], v[178:181], v[56:59]
	s_mov_b32 m0, s27
	v_mfma_f32_16x16x32_bf16 v[60:63], v[166:169], v[178:181], v[60:63]
	global_load_lds_dwordx4 v0, s[46:47]
	s_waitcnt lgkmcnt(3)
	v_mfma_f32_16x16x32_bf16 v[48:51], v[214:217], v[162:165], v[48:51]
	v_mfma_f32_16x16x32_bf16 v[64:67], v[214:217], v[178:181], v[64:67]
	s_waitcnt lgkmcnt(2)
	v_mfma_f32_16x16x32_bf16 v[174:177], v[218:221], v[162:165], v[174:177]
	ds_read_b128 v[162:165], v16
	v_mfma_f32_16x16x32_bf16 v[170:173], v[218:221], v[178:181], v[170:173]
	ds_read_b128 v[178:181], v17
	s_waitcnt lgkmcnt(3)
	s_mov_b32 m0, s28
	v_mfma_f32_16x16x32_bf16 v[72:75], v[158:161], v[222:225], v[72:75]
	global_load_lds_dwordx4 v0, s[48:49]
	v_mfma_f32_16x16x32_bf16 v[76:79], v[166:169], v[222:225], v[76:79]
	v_mfma_f32_16x16x32_bf16 v[80:83], v[214:217], v[222:225], v[80:83]
	v_mfma_f32_16x16x32_bf16 v[32:35], v[218:221], v[222:225], v[32:35]
	ds_read_b128 v[222:225], v18
	s_waitcnt lgkmcnt(3)
	v_mfma_f32_16x16x32_bf16 v[88:91], v[158:161], v[226:229], v[88:91]
	s_mov_b32 m0, s29
	v_mfma_f32_16x16x32_bf16 v[92:95], v[166:169], v[226:229], v[92:95]
	global_load_lds_dwordx4 v2, s[46:47]
	v_mfma_f32_16x16x32_bf16 v[96:99], v[214:217], v[226:229], v[96:99]
	v_mfma_f32_16x16x32_bf16 v[36:39], v[218:221], v[226:229], v[36:39]
	ds_read_b128 v[226:229], v19
	s_waitcnt lgkmcnt(3)
	v_mfma_f32_16x16x32_bf16 v[104:107], v[158:161], v[162:165], v[104:107]
	s_waitcnt lgkmcnt(2)
	v_mfma_f32_16x16x32_bf16 v[116:119], v[158:161], v[178:181], v[116:119]
	s_waitcnt lgkmcnt(1)
	s_mov_b32 m0, s30
	v_mfma_f32_16x16x32_bf16 v[128:131], v[158:161], v[222:225], v[128:131]
	global_load_lds_dwordx4 v2, s[48:49]
	s_waitcnt lgkmcnt(0)
	v_mfma_f32_16x16x32_bf16 v[100:103], v[158:161], v[226:229], v[100:103]
	ds_read_b128 v[158:161], v20
	v_mfma_f32_16x16x32_bf16 v[108:111], v[166:169], v[162:165], v[108:111]
	v_mfma_f32_16x16x32_bf16 v[120:123], v[166:169], v[178:181], v[120:123]
	v_mfma_f32_16x16x32_bf16 v[132:135], v[166:169], v[222:225], v[132:135]
	s_mov_b32 m0, s31
	v_mfma_f32_16x16x32_bf16 v[140:143], v[166:169], v[226:229], v[140:143]
	global_load_lds_dwordx4 v4, s[46:47]
	ds_read_b128 v[166:169], v24
	v_mfma_f32_16x16x32_bf16 v[112:115], v[214:217], v[162:165], v[112:115]
	v_mfma_f32_16x16x32_bf16 v[52:55], v[218:221], v[162:165], v[52:55]
	ds_read_b128 v[162:165], v21
	v_mfma_f32_16x16x32_bf16 v[124:127], v[214:217], v[178:181], v[124:127]
	v_mfma_f32_16x16x32_bf16 v[68:71], v[218:221], v[178:181], v[68:71]
	ds_read_b128 v[178:181], v25
	s_mov_b32 m0, s34
	v_mfma_f32_16x16x32_bf16 v[136:139], v[214:217], v[222:225], v[136:139]
	global_load_lds_dwordx4 v4, s[48:49]
	v_mfma_f32_16x16x32_bf16 v[84:87], v[218:221], v[222:225], v[84:87]
	ds_read_b128 v[222:225], v26
	v_mfma_f32_16x16x32_bf16 v[150:153], v[214:217], v[226:229], v[150:153]
	ds_read_b128 v[214:217], v23
	v_mfma_f32_16x16x32_bf16 v[154:157], v[218:221], v[226:229], v[154:157]
	ds_read_b128 v[218:221], v22
	ds_read_b128 v[226:229], v27
	s_waitcnt lgkmcnt(6)
	v_mfma_f32_16x16x32_bf16 v[40:43], v[158:161], v[166:169], v[40:43]
	s_waitcnt lgkmcnt(5)
	s_mov_b32 m0, s35
	v_mfma_f32_16x16x32_bf16 v[44:47], v[162:165], v[166:169], v[44:47]
	global_load_lds_dwordx4 v146, s[46:47]
	s_waitcnt lgkmcnt(4)
	v_mfma_f32_16x16x32_bf16 v[56:59], v[158:161], v[178:181], v[56:59]
	v_mfma_f32_16x16x32_bf16 v[60:63], v[162:165], v[178:181], v[60:63]
	s_waitcnt lgkmcnt(3)
	v_mfma_f32_16x16x32_bf16 v[72:75], v[158:161], v[222:225], v[72:75]
	v_mfma_f32_16x16x32_bf16 v[76:79], v[162:165], v[222:225], v[76:79]
	s_waitcnt lgkmcnt(2)
	s_mov_b32 m0, s36
	v_mfma_f32_16x16x32_bf16 v[48:51], v[214:217], v[166:169], v[48:51]
	global_load_lds_dwordx4 v146, s[48:49]
	s_waitcnt lgkmcnt(1)
	v_mfma_f32_16x16x32_bf16 v[174:177], v[218:221], v[166:169], v[174:177]
	ds_read_b128 v[166:169], v28
	v_mfma_f32_16x16x32_bf16 v[64:67], v[214:217], v[178:181], v[64:67]
	v_mfma_f32_16x16x32_bf16 v[170:173], v[218:221], v[178:181], v[170:173]
	ds_read_b128 v[178:181], v29
	v_mfma_f32_16x16x32_bf16 v[80:83], v[214:217], v[222:225], v[80:83]
	v_mfma_f32_16x16x32_bf16 v[32:35], v[218:221], v[222:225], v[32:35]
	ds_read_b128 v[222:225], v30
	s_waitcnt lgkmcnt(3)
	v_mfma_f32_16x16x32_bf16 v[88:91], v[158:161], v[226:229], v[88:91]
	v_mfma_f32_16x16x32_bf16 v[92:95], v[162:165], v[226:229], v[92:95]
	v_mfma_f32_16x16x32_bf16 v[96:99], v[214:217], v[226:229], v[96:99]
	v_mfma_f32_16x16x32_bf16 v[36:39], v[218:221], v[226:229], v[36:39]
	ds_read_b128 v[226:229], v31
	s_waitcnt lgkmcnt(3)
	v_mfma_f32_16x16x32_bf16 v[104:107], v[158:161], v[166:169], v[104:107]
	v_mfma_f32_16x16x32_bf16 v[108:111], v[162:165], v[166:169], v[108:111]
	v_mfma_f32_16x16x32_bf16 v[112:115], v[214:217], v[166:169], v[112:115]
	v_mfma_f32_16x16x32_bf16 v[52:55], v[218:221], v[166:169], v[52:55]
	s_waitcnt lgkmcnt(2)
	v_mfma_f32_16x16x32_bf16 v[116:119], v[158:161], v[178:181], v[116:119]
	v_mfma_f32_16x16x32_bf16 v[120:123], v[162:165], v[178:181], v[120:123]
	v_mfma_f32_16x16x32_bf16 v[124:127], v[214:217], v[178:181], v[124:127]
	v_mfma_f32_16x16x32_bf16 v[68:71], v[218:221], v[178:181], v[68:71]
	s_waitcnt lgkmcnt(1)
	v_mfma_f32_16x16x32_bf16 v[128:131], v[158:161], v[222:225], v[128:131]
	v_mfma_f32_16x16x32_bf16 v[132:135], v[162:165], v[222:225], v[132:135]
	v_mfma_f32_16x16x32_bf16 v[136:139], v[214:217], v[222:225], v[136:139]
	v_mfma_f32_16x16x32_bf16 v[84:87], v[218:221], v[222:225], v[84:87]
	s_waitcnt lgkmcnt(0)
	v_mfma_f32_16x16x32_bf16 v[100:103], v[158:161], v[226:229], v[100:103]
	v_mfma_f32_16x16x32_bf16 v[140:143], v[162:165], v[226:229], v[140:143]
	v_mfma_f32_16x16x32_bf16 v[150:153], v[214:217], v[226:229], v[150:153]
	v_mfma_f32_16x16x32_bf16 v[154:157], v[218:221], v[226:229], v[154:157]
	s_add_u32 s46, s0, 0x2980
	s_addc_u32 s47, s1, 0
	s_add_u32 s48, s14, 0x2980
	s_waitcnt vmcnt(0)
	s_barrier
	s_addc_u32 s49, s15, 0
	ds_read_b128 v[158:161], v7 offset:32768
	ds_read_b128 v[162:165], v6
	ds_read_b128 v[166:169], v7 offset:34816
	ds_read_b128 v[178:181], v6 offset:2048
	ds_read_b128 v[214:217], v7 offset:36864
	ds_read_b128 v[218:221], v7 offset:38912
	ds_read_b128 v[222:225], v6 offset:4096
	ds_read_b128 v[226:229], v6 offset:6144
	s_waitcnt lgkmcnt(6)
	v_mfma_f32_16x16x32_bf16 v[40:43], v[158:161], v[162:165], v[40:43]
	s_waitcnt lgkmcnt(5)
	v_mfma_f32_16x16x32_bf16 v[44:47], v[166:169], v[162:165], v[44:47]
	s_waitcnt lgkmcnt(4)
	v_mfma_f32_16x16x32_bf16 v[56:59], v[158:161], v[178:181], v[56:59]
	s_mov_b32 m0, s38
	v_mfma_f32_16x16x32_bf16 v[60:63], v[166:169], v[178:181], v[60:63]
	global_load_lds_dwordx4 v0, s[46:47]
	s_waitcnt lgkmcnt(3)
	v_mfma_f32_16x16x32_bf16 v[48:51], v[214:217], v[162:165], v[48:51]
	v_mfma_f32_16x16x32_bf16 v[64:67], v[214:217], v[178:181], v[64:67]
	s_waitcnt lgkmcnt(2)
	v_mfma_f32_16x16x32_bf16 v[174:177], v[218:221], v[162:165], v[174:177]
	ds_read_b128 v[162:165], v6 offset:8192
	v_mfma_f32_16x16x32_bf16 v[170:173], v[218:221], v[178:181], v[170:173]
	ds_read_b128 v[178:181], v6 offset:10240
	s_waitcnt lgkmcnt(3)
	s_mov_b32 m0, s37
	v_mfma_f32_16x16x32_bf16 v[72:75], v[158:161], v[222:225], v[72:75]
	global_load_lds_dwordx4 v0, s[48:49]
	v_mfma_f32_16x16x32_bf16 v[76:79], v[166:169], v[222:225], v[76:79]
	v_mfma_f32_16x16x32_bf16 v[80:83], v[214:217], v[222:225], v[80:83]
	v_mfma_f32_16x16x32_bf16 v[32:35], v[218:221], v[222:225], v[32:35]
	ds_read_b128 v[222:225], v6 offset:12288
	s_waitcnt lgkmcnt(3)
	v_mfma_f32_16x16x32_bf16 v[88:91], v[158:161], v[226:229], v[88:91]
	s_mov_b32 m0, s39
	v_mfma_f32_16x16x32_bf16 v[92:95], v[166:169], v[226:229], v[92:95]
	global_load_lds_dwordx4 v2, s[46:47]
	v_mfma_f32_16x16x32_bf16 v[96:99], v[214:217], v[226:229], v[96:99]
	v_mfma_f32_16x16x32_bf16 v[36:39], v[218:221], v[226:229], v[36:39]
	ds_read_b128 v[226:229], v6 offset:14336
	s_waitcnt lgkmcnt(3)
	v_mfma_f32_16x16x32_bf16 v[104:107], v[158:161], v[162:165], v[104:107]
	s_waitcnt lgkmcnt(2)
	v_mfma_f32_16x16x32_bf16 v[116:119], v[158:161], v[178:181], v[116:119]
	s_waitcnt lgkmcnt(1)
	s_mov_b32 m0, s40
	v_mfma_f32_16x16x32_bf16 v[128:131], v[158:161], v[222:225], v[128:131]
	global_load_lds_dwordx4 v2, s[48:49]
	s_waitcnt lgkmcnt(0)
	v_mfma_f32_16x16x32_bf16 v[100:103], v[158:161], v[226:229], v[100:103]
	ds_read_b128 v[158:161], v7 offset:33792
	v_mfma_f32_16x16x32_bf16 v[108:111], v[166:169], v[162:165], v[108:111]
	v_mfma_f32_16x16x32_bf16 v[120:123], v[166:169], v[178:181], v[120:123]
	v_mfma_f32_16x16x32_bf16 v[132:135], v[166:169], v[222:225], v[132:135]
	s_mov_b32 m0, s41
	v_mfma_f32_16x16x32_bf16 v[140:143], v[166:169], v[226:229], v[140:143]
	global_load_lds_dwordx4 v4, s[46:47]
	ds_read_b128 v[166:169], v6 offset:1024
	v_mfma_f32_16x16x32_bf16 v[112:115], v[214:217], v[162:165], v[112:115]
	v_mfma_f32_16x16x32_bf16 v[52:55], v[218:221], v[162:165], v[52:55]
	ds_read_b128 v[162:165], v7 offset:35840
	v_mfma_f32_16x16x32_bf16 v[124:127], v[214:217], v[178:181], v[124:127]
	v_mfma_f32_16x16x32_bf16 v[68:71], v[218:221], v[178:181], v[68:71]
	ds_read_b128 v[178:181], v6 offset:3072
	s_mov_b32 m0, s42
	v_mfma_f32_16x16x32_bf16 v[136:139], v[214:217], v[222:225], v[136:139]
	global_load_lds_dwordx4 v4, s[48:49]
	v_mfma_f32_16x16x32_bf16 v[84:87], v[218:221], v[222:225], v[84:87]
	ds_read_b128 v[222:225], v6 offset:5120
	v_mfma_f32_16x16x32_bf16 v[150:153], v[214:217], v[226:229], v[150:153]
	ds_read_b128 v[214:217], v7 offset:37888
	v_mfma_f32_16x16x32_bf16 v[154:157], v[218:221], v[226:229], v[154:157]
	ds_read_b128 v[218:221], v7 offset:39936
	ds_read_b128 v[226:229], v6 offset:7168
	s_waitcnt lgkmcnt(6)
	v_mfma_f32_16x16x32_bf16 v[40:43], v[158:161], v[166:169], v[40:43]
	s_waitcnt lgkmcnt(5)
	s_mov_b32 m0, s43
	v_mfma_f32_16x16x32_bf16 v[44:47], v[162:165], v[166:169], v[44:47]
	global_load_lds_dwordx4 v146, s[46:47]
	s_waitcnt lgkmcnt(4)
	v_mfma_f32_16x16x32_bf16 v[56:59], v[158:161], v[178:181], v[56:59]
	v_mfma_f32_16x16x32_bf16 v[60:63], v[162:165], v[178:181], v[60:63]
	s_waitcnt lgkmcnt(3)
	v_mfma_f32_16x16x32_bf16 v[72:75], v[158:161], v[222:225], v[72:75]
	v_mfma_f32_16x16x32_bf16 v[76:79], v[162:165], v[222:225], v[76:79]
	s_waitcnt lgkmcnt(2)
	s_mov_b32 m0, s44
	v_mfma_f32_16x16x32_bf16 v[48:51], v[214:217], v[166:169], v[48:51]
	global_load_lds_dwordx4 v146, s[48:49]
	s_waitcnt lgkmcnt(1)
	v_mfma_f32_16x16x32_bf16 v[174:177], v[218:221], v[166:169], v[174:177]
	ds_read_b128 v[166:169], v6 offset:9216
	v_mfma_f32_16x16x32_bf16 v[64:67], v[214:217], v[178:181], v[64:67]
	v_mfma_f32_16x16x32_bf16 v[170:173], v[218:221], v[178:181], v[170:173]
	ds_read_b128 v[178:181], v6 offset:11264
	v_mfma_f32_16x16x32_bf16 v[80:83], v[214:217], v[222:225], v[80:83]
	v_mfma_f32_16x16x32_bf16 v[32:35], v[218:221], v[222:225], v[32:35]
	ds_read_b128 v[222:225], v6 offset:13312
	s_waitcnt lgkmcnt(3)
	v_mfma_f32_16x16x32_bf16 v[88:91], v[158:161], v[226:229], v[88:91]
	v_mfma_f32_16x16x32_bf16 v[92:95], v[162:165], v[226:229], v[92:95]
	v_mfma_f32_16x16x32_bf16 v[96:99], v[214:217], v[226:229], v[96:99]
	v_mfma_f32_16x16x32_bf16 v[36:39], v[218:221], v[226:229], v[36:39]
	ds_read_b128 v[226:229], v6 offset:15360
	s_waitcnt lgkmcnt(3)
	v_mfma_f32_16x16x32_bf16 v[104:107], v[158:161], v[166:169], v[104:107]
	v_mfma_f32_16x16x32_bf16 v[108:111], v[162:165], v[166:169], v[108:111]
	v_mfma_f32_16x16x32_bf16 v[112:115], v[214:217], v[166:169], v[112:115]
	v_mfma_f32_16x16x32_bf16 v[52:55], v[218:221], v[166:169], v[52:55]
	s_waitcnt lgkmcnt(2)
	v_mfma_f32_16x16x32_bf16 v[116:119], v[158:161], v[178:181], v[116:119]
	v_mfma_f32_16x16x32_bf16 v[120:123], v[162:165], v[178:181], v[120:123]
	v_mfma_f32_16x16x32_bf16 v[124:127], v[214:217], v[178:181], v[124:127]
	v_mfma_f32_16x16x32_bf16 v[68:71], v[218:221], v[178:181], v[68:71]
	s_waitcnt lgkmcnt(1)
	v_mfma_f32_16x16x32_bf16 v[128:131], v[158:161], v[222:225], v[128:131]
	v_mfma_f32_16x16x32_bf16 v[132:135], v[162:165], v[222:225], v[132:135]
	v_mfma_f32_16x16x32_bf16 v[136:139], v[214:217], v[222:225], v[136:139]
	v_mfma_f32_16x16x32_bf16 v[84:87], v[218:221], v[222:225], v[84:87]
	s_waitcnt lgkmcnt(0)
	v_mfma_f32_16x16x32_bf16 v[100:103], v[158:161], v[226:229], v[100:103]
	v_mfma_f32_16x16x32_bf16 v[140:143], v[162:165], v[226:229], v[140:143]
	v_mfma_f32_16x16x32_bf16 v[150:153], v[214:217], v[226:229], v[150:153]
	v_mfma_f32_16x16x32_bf16 v[154:157], v[218:221], v[226:229], v[154:157]
	s_add_u32 s46, s0, 0x2a00
	s_addc_u32 s47, s1, 0
	s_add_u32 s48, s14, 0x2a00
	s_waitcnt vmcnt(0)
	s_barrier
	s_addc_u32 s49, s15, 0
	ds_read_b128 v[158:161], v8
	ds_read_b128 v[162:165], v12
	ds_read_b128 v[166:169], v9
	ds_read_b128 v[178:181], v13
	ds_read_b128 v[214:217], v11
	ds_read_b128 v[218:221], v10
	ds_read_b128 v[222:225], v14
	ds_read_b128 v[226:229], v15
	s_waitcnt lgkmcnt(6)
	v_mfma_f32_16x16x32_bf16 v[40:43], v[158:161], v[162:165], v[40:43]
	s_waitcnt lgkmcnt(5)
	v_mfma_f32_16x16x32_bf16 v[44:47], v[166:169], v[162:165], v[44:47]
	s_waitcnt lgkmcnt(4)
	v_mfma_f32_16x16x32_bf16 v[56:59], v[158:161], v[178:181], v[56:59]
	s_mov_b32 m0, s27
	v_mfma_f32_16x16x32_bf16 v[60:63], v[166:169], v[178:181], v[60:63]
	global_load_lds_dwordx4 v0, s[46:47]
	s_waitcnt lgkmcnt(3)
	v_mfma_f32_16x16x32_bf16 v[48:51], v[214:217], v[162:165], v[48:51]
	v_mfma_f32_16x16x32_bf16 v[64:67], v[214:217], v[178:181], v[64:67]
	s_waitcnt lgkmcnt(2)
	v_mfma_f32_16x16x32_bf16 v[174:177], v[218:221], v[162:165], v[174:177]
	ds_read_b128 v[162:165], v16
	v_mfma_f32_16x16x32_bf16 v[170:173], v[218:221], v[178:181], v[170:173]
	ds_read_b128 v[178:181], v17
	s_waitcnt lgkmcnt(3)
	s_mov_b32 m0, s28
	v_mfma_f32_16x16x32_bf16 v[72:75], v[158:161], v[222:225], v[72:75]
	global_load_lds_dwordx4 v0, s[48:49]
	v_mfma_f32_16x16x32_bf16 v[76:79], v[166:169], v[222:225], v[76:79]
	v_mfma_f32_16x16x32_bf16 v[80:83], v[214:217], v[222:225], v[80:83]
	v_mfma_f32_16x16x32_bf16 v[32:35], v[218:221], v[222:225], v[32:35]
	ds_read_b128 v[222:225], v18
	s_waitcnt lgkmcnt(3)
	v_mfma_f32_16x16x32_bf16 v[88:91], v[158:161], v[226:229], v[88:91]
	s_mov_b32 m0, s29
	v_mfma_f32_16x16x32_bf16 v[92:95], v[166:169], v[226:229], v[92:95]
	global_load_lds_dwordx4 v2, s[46:47]
	v_mfma_f32_16x16x32_bf16 v[96:99], v[214:217], v[226:229], v[96:99]
	v_mfma_f32_16x16x32_bf16 v[36:39], v[218:221], v[226:229], v[36:39]
	ds_read_b128 v[226:229], v19
	s_waitcnt lgkmcnt(3)
	v_mfma_f32_16x16x32_bf16 v[104:107], v[158:161], v[162:165], v[104:107]
	s_waitcnt lgkmcnt(2)
	v_mfma_f32_16x16x32_bf16 v[116:119], v[158:161], v[178:181], v[116:119]
	s_waitcnt lgkmcnt(1)
	s_mov_b32 m0, s30
	v_mfma_f32_16x16x32_bf16 v[128:131], v[158:161], v[222:225], v[128:131]
	global_load_lds_dwordx4 v2, s[48:49]
	s_waitcnt lgkmcnt(0)
	v_mfma_f32_16x16x32_bf16 v[100:103], v[158:161], v[226:229], v[100:103]
	ds_read_b128 v[158:161], v20
	v_mfma_f32_16x16x32_bf16 v[108:111], v[166:169], v[162:165], v[108:111]
	v_mfma_f32_16x16x32_bf16 v[120:123], v[166:169], v[178:181], v[120:123]
	v_mfma_f32_16x16x32_bf16 v[132:135], v[166:169], v[222:225], v[132:135]
	s_mov_b32 m0, s31
	v_mfma_f32_16x16x32_bf16 v[140:143], v[166:169], v[226:229], v[140:143]
	global_load_lds_dwordx4 v4, s[46:47]
	ds_read_b128 v[166:169], v24
	v_mfma_f32_16x16x32_bf16 v[112:115], v[214:217], v[162:165], v[112:115]
	v_mfma_f32_16x16x32_bf16 v[52:55], v[218:221], v[162:165], v[52:55]
	ds_read_b128 v[162:165], v21
	v_mfma_f32_16x16x32_bf16 v[124:127], v[214:217], v[178:181], v[124:127]
	v_mfma_f32_16x16x32_bf16 v[68:71], v[218:221], v[178:181], v[68:71]
	ds_read_b128 v[178:181], v25
	s_mov_b32 m0, s34
	v_mfma_f32_16x16x32_bf16 v[136:139], v[214:217], v[222:225], v[136:139]
	global_load_lds_dwordx4 v4, s[48:49]
	v_mfma_f32_16x16x32_bf16 v[84:87], v[218:221], v[222:225], v[84:87]
	ds_read_b128 v[222:225], v26
	v_mfma_f32_16x16x32_bf16 v[150:153], v[214:217], v[226:229], v[150:153]
	ds_read_b128 v[214:217], v23
	v_mfma_f32_16x16x32_bf16 v[154:157], v[218:221], v[226:229], v[154:157]
	ds_read_b128 v[218:221], v22
	ds_read_b128 v[226:229], v27
	s_waitcnt lgkmcnt(6)
	v_mfma_f32_16x16x32_bf16 v[40:43], v[158:161], v[166:169], v[40:43]
	s_waitcnt lgkmcnt(5)
	s_mov_b32 m0, s35
	v_mfma_f32_16x16x32_bf16 v[44:47], v[162:165], v[166:169], v[44:47]
	global_load_lds_dwordx4 v146, s[46:47]
	s_waitcnt lgkmcnt(4)
	v_mfma_f32_16x16x32_bf16 v[56:59], v[158:161], v[178:181], v[56:59]
	v_mfma_f32_16x16x32_bf16 v[60:63], v[162:165], v[178:181], v[60:63]
	s_waitcnt lgkmcnt(3)
	v_mfma_f32_16x16x32_bf16 v[72:75], v[158:161], v[222:225], v[72:75]
	v_mfma_f32_16x16x32_bf16 v[76:79], v[162:165], v[222:225], v[76:79]
	s_waitcnt lgkmcnt(2)
	s_mov_b32 m0, s36
	v_mfma_f32_16x16x32_bf16 v[48:51], v[214:217], v[166:169], v[48:51]
	global_load_lds_dwordx4 v146, s[48:49]
	s_waitcnt lgkmcnt(1)
	v_mfma_f32_16x16x32_bf16 v[174:177], v[218:221], v[166:169], v[174:177]
	ds_read_b128 v[166:169], v28
	v_mfma_f32_16x16x32_bf16 v[64:67], v[214:217], v[178:181], v[64:67]
	v_mfma_f32_16x16x32_bf16 v[170:173], v[218:221], v[178:181], v[170:173]
	ds_read_b128 v[178:181], v29
	v_mfma_f32_16x16x32_bf16 v[80:83], v[214:217], v[222:225], v[80:83]
	v_mfma_f32_16x16x32_bf16 v[32:35], v[218:221], v[222:225], v[32:35]
	ds_read_b128 v[222:225], v30
	s_waitcnt lgkmcnt(3)
	v_mfma_f32_16x16x32_bf16 v[88:91], v[158:161], v[226:229], v[88:91]
	v_mfma_f32_16x16x32_bf16 v[92:95], v[162:165], v[226:229], v[92:95]
	v_mfma_f32_16x16x32_bf16 v[96:99], v[214:217], v[226:229], v[96:99]
	v_mfma_f32_16x16x32_bf16 v[36:39], v[218:221], v[226:229], v[36:39]
	ds_read_b128 v[226:229], v31
	s_waitcnt lgkmcnt(3)
	v_mfma_f32_16x16x32_bf16 v[104:107], v[158:161], v[166:169], v[104:107]
	v_mfma_f32_16x16x32_bf16 v[108:111], v[162:165], v[166:169], v[108:111]
	v_mfma_f32_16x16x32_bf16 v[112:115], v[214:217], v[166:169], v[112:115]
	v_mfma_f32_16x16x32_bf16 v[52:55], v[218:221], v[166:169], v[52:55]
	s_waitcnt lgkmcnt(2)
	v_mfma_f32_16x16x32_bf16 v[116:119], v[158:161], v[178:181], v[116:119]
	v_mfma_f32_16x16x32_bf16 v[120:123], v[162:165], v[178:181], v[120:123]
	v_mfma_f32_16x16x32_bf16 v[124:127], v[214:217], v[178:181], v[124:127]
	v_mfma_f32_16x16x32_bf16 v[68:71], v[218:221], v[178:181], v[68:71]
	s_waitcnt lgkmcnt(1)
	v_mfma_f32_16x16x32_bf16 v[128:131], v[158:161], v[222:225], v[128:131]
	v_mfma_f32_16x16x32_bf16 v[132:135], v[162:165], v[222:225], v[132:135]
	v_mfma_f32_16x16x32_bf16 v[136:139], v[214:217], v[222:225], v[136:139]
	v_mfma_f32_16x16x32_bf16 v[84:87], v[218:221], v[222:225], v[84:87]
	s_waitcnt lgkmcnt(0)
	v_mfma_f32_16x16x32_bf16 v[100:103], v[158:161], v[226:229], v[100:103]
	v_mfma_f32_16x16x32_bf16 v[140:143], v[162:165], v[226:229], v[140:143]
	v_mfma_f32_16x16x32_bf16 v[150:153], v[214:217], v[226:229], v[150:153]
	v_mfma_f32_16x16x32_bf16 v[154:157], v[218:221], v[226:229], v[154:157]
	s_add_u32 s46, s0, 0x2a80
	s_addc_u32 s47, s1, 0
	s_add_u32 s48, s14, 0x2a80
	s_waitcnt vmcnt(0)
	s_barrier
	s_addc_u32 s49, s15, 0
	ds_read_b128 v[158:161], v7 offset:32768
	ds_read_b128 v[162:165], v6
	ds_read_b128 v[166:169], v7 offset:34816
	ds_read_b128 v[178:181], v6 offset:2048
	ds_read_b128 v[214:217], v7 offset:36864
	ds_read_b128 v[218:221], v7 offset:38912
	ds_read_b128 v[222:225], v6 offset:4096
	ds_read_b128 v[226:229], v6 offset:6144
	s_waitcnt lgkmcnt(6)
	v_mfma_f32_16x16x32_bf16 v[40:43], v[158:161], v[162:165], v[40:43]
	s_waitcnt lgkmcnt(5)
	v_mfma_f32_16x16x32_bf16 v[44:47], v[166:169], v[162:165], v[44:47]
	s_waitcnt lgkmcnt(4)
	v_mfma_f32_16x16x32_bf16 v[56:59], v[158:161], v[178:181], v[56:59]
	s_mov_b32 m0, s38
	v_mfma_f32_16x16x32_bf16 v[60:63], v[166:169], v[178:181], v[60:63]
	global_load_lds_dwordx4 v0, s[46:47]
	s_waitcnt lgkmcnt(3)
	v_mfma_f32_16x16x32_bf16 v[48:51], v[214:217], v[162:165], v[48:51]
	v_mfma_f32_16x16x32_bf16 v[64:67], v[214:217], v[178:181], v[64:67]
	s_waitcnt lgkmcnt(2)
	v_mfma_f32_16x16x32_bf16 v[174:177], v[218:221], v[162:165], v[174:177]
	ds_read_b128 v[162:165], v6 offset:8192
	v_mfma_f32_16x16x32_bf16 v[170:173], v[218:221], v[178:181], v[170:173]
	ds_read_b128 v[178:181], v6 offset:10240
	s_waitcnt lgkmcnt(3)
	s_mov_b32 m0, s37
	v_mfma_f32_16x16x32_bf16 v[72:75], v[158:161], v[222:225], v[72:75]
	global_load_lds_dwordx4 v0, s[48:49]
	v_mfma_f32_16x16x32_bf16 v[76:79], v[166:169], v[222:225], v[76:79]
	v_mfma_f32_16x16x32_bf16 v[80:83], v[214:217], v[222:225], v[80:83]
	v_mfma_f32_16x16x32_bf16 v[32:35], v[218:221], v[222:225], v[32:35]
	ds_read_b128 v[222:225], v6 offset:12288
	s_waitcnt lgkmcnt(3)
	v_mfma_f32_16x16x32_bf16 v[88:91], v[158:161], v[226:229], v[88:91]
	s_mov_b32 m0, s39
	v_mfma_f32_16x16x32_bf16 v[92:95], v[166:169], v[226:229], v[92:95]
	global_load_lds_dwordx4 v2, s[46:47]
	v_mfma_f32_16x16x32_bf16 v[96:99], v[214:217], v[226:229], v[96:99]
	v_mfma_f32_16x16x32_bf16 v[36:39], v[218:221], v[226:229], v[36:39]
	ds_read_b128 v[226:229], v6 offset:14336
	s_waitcnt lgkmcnt(3)
	v_mfma_f32_16x16x32_bf16 v[104:107], v[158:161], v[162:165], v[104:107]
	s_waitcnt lgkmcnt(2)
	v_mfma_f32_16x16x32_bf16 v[116:119], v[158:161], v[178:181], v[116:119]
	s_waitcnt lgkmcnt(1)
	s_mov_b32 m0, s40
	v_mfma_f32_16x16x32_bf16 v[128:131], v[158:161], v[222:225], v[128:131]
	global_load_lds_dwordx4 v2, s[48:49]
	s_waitcnt lgkmcnt(0)
	v_mfma_f32_16x16x32_bf16 v[100:103], v[158:161], v[226:229], v[100:103]
	ds_read_b128 v[158:161], v7 offset:33792
	v_mfma_f32_16x16x32_bf16 v[108:111], v[166:169], v[162:165], v[108:111]
	v_mfma_f32_16x16x32_bf16 v[120:123], v[166:169], v[178:181], v[120:123]
	v_mfma_f32_16x16x32_bf16 v[132:135], v[166:169], v[222:225], v[132:135]
	s_mov_b32 m0, s41
	v_mfma_f32_16x16x32_bf16 v[140:143], v[166:169], v[226:229], v[140:143]
	global_load_lds_dwordx4 v4, s[46:47]
	ds_read_b128 v[166:169], v6 offset:1024
	v_mfma_f32_16x16x32_bf16 v[112:115], v[214:217], v[162:165], v[112:115]
	v_mfma_f32_16x16x32_bf16 v[52:55], v[218:221], v[162:165], v[52:55]
	ds_read_b128 v[162:165], v7 offset:35840
	v_mfma_f32_16x16x32_bf16 v[124:127], v[214:217], v[178:181], v[124:127]
	v_mfma_f32_16x16x32_bf16 v[68:71], v[218:221], v[178:181], v[68:71]
	ds_read_b128 v[178:181], v6 offset:3072
	s_mov_b32 m0, s42
	v_mfma_f32_16x16x32_bf16 v[136:139], v[214:217], v[222:225], v[136:139]
	global_load_lds_dwordx4 v4, s[48:49]
	v_mfma_f32_16x16x32_bf16 v[84:87], v[218:221], v[222:225], v[84:87]
	ds_read_b128 v[222:225], v6 offset:5120
	v_mfma_f32_16x16x32_bf16 v[150:153], v[214:217], v[226:229], v[150:153]
	ds_read_b128 v[214:217], v7 offset:37888
	v_mfma_f32_16x16x32_bf16 v[154:157], v[218:221], v[226:229], v[154:157]
	ds_read_b128 v[218:221], v7 offset:39936
	ds_read_b128 v[226:229], v6 offset:7168
	s_waitcnt lgkmcnt(6)
	v_mfma_f32_16x16x32_bf16 v[40:43], v[158:161], v[166:169], v[40:43]
	s_waitcnt lgkmcnt(5)
	s_mov_b32 m0, s43
	v_mfma_f32_16x16x32_bf16 v[44:47], v[162:165], v[166:169], v[44:47]
	global_load_lds_dwordx4 v146, s[46:47]
	s_waitcnt lgkmcnt(4)
	v_mfma_f32_16x16x32_bf16 v[56:59], v[158:161], v[178:181], v[56:59]
	v_mfma_f32_16x16x32_bf16 v[60:63], v[162:165], v[178:181], v[60:63]
	s_waitcnt lgkmcnt(3)
	v_mfma_f32_16x16x32_bf16 v[72:75], v[158:161], v[222:225], v[72:75]
	v_mfma_f32_16x16x32_bf16 v[76:79], v[162:165], v[222:225], v[76:79]
	s_waitcnt lgkmcnt(2)
	s_mov_b32 m0, s44
	v_mfma_f32_16x16x32_bf16 v[48:51], v[214:217], v[166:169], v[48:51]
	global_load_lds_dwordx4 v146, s[48:49]
	s_waitcnt lgkmcnt(1)
	v_mfma_f32_16x16x32_bf16 v[174:177], v[218:221], v[166:169], v[174:177]
	ds_read_b128 v[166:169], v6 offset:9216
	v_mfma_f32_16x16x32_bf16 v[64:67], v[214:217], v[178:181], v[64:67]
	v_mfma_f32_16x16x32_bf16 v[170:173], v[218:221], v[178:181], v[170:173]
	ds_read_b128 v[178:181], v6 offset:11264
	v_mfma_f32_16x16x32_bf16 v[80:83], v[214:217], v[222:225], v[80:83]
	v_mfma_f32_16x16x32_bf16 v[32:35], v[218:221], v[222:225], v[32:35]
	ds_read_b128 v[222:225], v6 offset:13312
	s_waitcnt lgkmcnt(3)
	v_mfma_f32_16x16x32_bf16 v[88:91], v[158:161], v[226:229], v[88:91]
	v_mfma_f32_16x16x32_bf16 v[92:95], v[162:165], v[226:229], v[92:95]
	v_mfma_f32_16x16x32_bf16 v[96:99], v[214:217], v[226:229], v[96:99]
	v_mfma_f32_16x16x32_bf16 v[36:39], v[218:221], v[226:229], v[36:39]
	ds_read_b128 v[226:229], v6 offset:15360
	s_waitcnt lgkmcnt(3)
	v_mfma_f32_16x16x32_bf16 v[104:107], v[158:161], v[166:169], v[104:107]
	v_mfma_f32_16x16x32_bf16 v[108:111], v[162:165], v[166:169], v[108:111]
	v_mfma_f32_16x16x32_bf16 v[112:115], v[214:217], v[166:169], v[112:115]
	v_mfma_f32_16x16x32_bf16 v[52:55], v[218:221], v[166:169], v[52:55]
	s_waitcnt lgkmcnt(2)
	v_mfma_f32_16x16x32_bf16 v[116:119], v[158:161], v[178:181], v[116:119]
	v_mfma_f32_16x16x32_bf16 v[120:123], v[162:165], v[178:181], v[120:123]
	v_mfma_f32_16x16x32_bf16 v[124:127], v[214:217], v[178:181], v[124:127]
	v_mfma_f32_16x16x32_bf16 v[68:71], v[218:221], v[178:181], v[68:71]
	s_waitcnt lgkmcnt(1)
	v_mfma_f32_16x16x32_bf16 v[128:131], v[158:161], v[222:225], v[128:131]
	v_mfma_f32_16x16x32_bf16 v[132:135], v[162:165], v[222:225], v[132:135]
	v_mfma_f32_16x16x32_bf16 v[136:139], v[214:217], v[222:225], v[136:139]
	v_mfma_f32_16x16x32_bf16 v[84:87], v[218:221], v[222:225], v[84:87]
	s_waitcnt lgkmcnt(0)
	v_mfma_f32_16x16x32_bf16 v[100:103], v[158:161], v[226:229], v[100:103]
	v_mfma_f32_16x16x32_bf16 v[140:143], v[162:165], v[226:229], v[140:143]
	v_mfma_f32_16x16x32_bf16 v[150:153], v[214:217], v[226:229], v[150:153]
	v_mfma_f32_16x16x32_bf16 v[154:157], v[218:221], v[226:229], v[154:157]
	s_add_u32 s46, s0, 0x2b00
	s_addc_u32 s47, s1, 0
	s_add_u32 s48, s14, 0x2b00
	s_waitcnt vmcnt(0)
	s_barrier
	s_addc_u32 s49, s15, 0
	ds_read_b128 v[158:161], v8
	ds_read_b128 v[162:165], v12
	ds_read_b128 v[166:169], v9
	ds_read_b128 v[178:181], v13
	ds_read_b128 v[214:217], v11
	ds_read_b128 v[218:221], v10
	ds_read_b128 v[222:225], v14
	ds_read_b128 v[226:229], v15
	s_waitcnt lgkmcnt(6)
	v_mfma_f32_16x16x32_bf16 v[40:43], v[158:161], v[162:165], v[40:43]
	s_waitcnt lgkmcnt(5)
	v_mfma_f32_16x16x32_bf16 v[44:47], v[166:169], v[162:165], v[44:47]
	s_waitcnt lgkmcnt(4)
	v_mfma_f32_16x16x32_bf16 v[56:59], v[158:161], v[178:181], v[56:59]
	s_mov_b32 m0, s27
	v_mfma_f32_16x16x32_bf16 v[60:63], v[166:169], v[178:181], v[60:63]
	global_load_lds_dwordx4 v0, s[46:47]
	s_waitcnt lgkmcnt(3)
	v_mfma_f32_16x16x32_bf16 v[48:51], v[214:217], v[162:165], v[48:51]
	v_mfma_f32_16x16x32_bf16 v[64:67], v[214:217], v[178:181], v[64:67]
	s_waitcnt lgkmcnt(2)
	v_mfma_f32_16x16x32_bf16 v[174:177], v[218:221], v[162:165], v[174:177]
	ds_read_b128 v[162:165], v16
	v_mfma_f32_16x16x32_bf16 v[170:173], v[218:221], v[178:181], v[170:173]
	ds_read_b128 v[178:181], v17
	s_waitcnt lgkmcnt(3)
	s_mov_b32 m0, s28
	v_mfma_f32_16x16x32_bf16 v[72:75], v[158:161], v[222:225], v[72:75]
	global_load_lds_dwordx4 v0, s[48:49]
	v_mfma_f32_16x16x32_bf16 v[76:79], v[166:169], v[222:225], v[76:79]
	v_mfma_f32_16x16x32_bf16 v[80:83], v[214:217], v[222:225], v[80:83]
	v_mfma_f32_16x16x32_bf16 v[32:35], v[218:221], v[222:225], v[32:35]
	ds_read_b128 v[222:225], v18
	s_waitcnt lgkmcnt(3)
	v_mfma_f32_16x16x32_bf16 v[88:91], v[158:161], v[226:229], v[88:91]
	s_mov_b32 m0, s29
	v_mfma_f32_16x16x32_bf16 v[92:95], v[166:169], v[226:229], v[92:95]
	global_load_lds_dwordx4 v2, s[46:47]
	v_mfma_f32_16x16x32_bf16 v[96:99], v[214:217], v[226:229], v[96:99]
	v_mfma_f32_16x16x32_bf16 v[36:39], v[218:221], v[226:229], v[36:39]
	ds_read_b128 v[226:229], v19
	s_waitcnt lgkmcnt(3)
	v_mfma_f32_16x16x32_bf16 v[104:107], v[158:161], v[162:165], v[104:107]
	s_waitcnt lgkmcnt(2)
	v_mfma_f32_16x16x32_bf16 v[116:119], v[158:161], v[178:181], v[116:119]
	s_waitcnt lgkmcnt(1)
	s_mov_b32 m0, s30
	v_mfma_f32_16x16x32_bf16 v[128:131], v[158:161], v[222:225], v[128:131]
	global_load_lds_dwordx4 v2, s[48:49]
	s_waitcnt lgkmcnt(0)
	v_mfma_f32_16x16x32_bf16 v[100:103], v[158:161], v[226:229], v[100:103]
	ds_read_b128 v[158:161], v20
	v_mfma_f32_16x16x32_bf16 v[108:111], v[166:169], v[162:165], v[108:111]
	v_mfma_f32_16x16x32_bf16 v[120:123], v[166:169], v[178:181], v[120:123]
	v_mfma_f32_16x16x32_bf16 v[132:135], v[166:169], v[222:225], v[132:135]
	s_mov_b32 m0, s31
	v_mfma_f32_16x16x32_bf16 v[140:143], v[166:169], v[226:229], v[140:143]
	global_load_lds_dwordx4 v4, s[46:47]
	ds_read_b128 v[166:169], v24
	v_mfma_f32_16x16x32_bf16 v[112:115], v[214:217], v[162:165], v[112:115]
	v_mfma_f32_16x16x32_bf16 v[52:55], v[218:221], v[162:165], v[52:55]
	ds_read_b128 v[162:165], v21
	v_mfma_f32_16x16x32_bf16 v[124:127], v[214:217], v[178:181], v[124:127]
	v_mfma_f32_16x16x32_bf16 v[68:71], v[218:221], v[178:181], v[68:71]
	ds_read_b128 v[178:181], v25
	s_mov_b32 m0, s34
	v_mfma_f32_16x16x32_bf16 v[136:139], v[214:217], v[222:225], v[136:139]
	global_load_lds_dwordx4 v4, s[48:49]
	v_mfma_f32_16x16x32_bf16 v[84:87], v[218:221], v[222:225], v[84:87]
	ds_read_b128 v[222:225], v26
	v_mfma_f32_16x16x32_bf16 v[150:153], v[214:217], v[226:229], v[150:153]
	ds_read_b128 v[214:217], v23
	v_mfma_f32_16x16x32_bf16 v[154:157], v[218:221], v[226:229], v[154:157]
	ds_read_b128 v[218:221], v22
	ds_read_b128 v[226:229], v27
	s_waitcnt lgkmcnt(6)
	v_mfma_f32_16x16x32_bf16 v[40:43], v[158:161], v[166:169], v[40:43]
	s_waitcnt lgkmcnt(5)
	s_mov_b32 m0, s35
	v_mfma_f32_16x16x32_bf16 v[44:47], v[162:165], v[166:169], v[44:47]
	global_load_lds_dwordx4 v146, s[46:47]
	s_waitcnt lgkmcnt(4)
	v_mfma_f32_16x16x32_bf16 v[56:59], v[158:161], v[178:181], v[56:59]
	v_mfma_f32_16x16x32_bf16 v[60:63], v[162:165], v[178:181], v[60:63]
	s_waitcnt lgkmcnt(3)
	v_mfma_f32_16x16x32_bf16 v[72:75], v[158:161], v[222:225], v[72:75]
	v_mfma_f32_16x16x32_bf16 v[76:79], v[162:165], v[222:225], v[76:79]
	s_waitcnt lgkmcnt(2)
	s_mov_b32 m0, s36
	v_mfma_f32_16x16x32_bf16 v[48:51], v[214:217], v[166:169], v[48:51]
	global_load_lds_dwordx4 v146, s[48:49]
	s_waitcnt lgkmcnt(1)
	v_mfma_f32_16x16x32_bf16 v[174:177], v[218:221], v[166:169], v[174:177]
	ds_read_b128 v[166:169], v28
	v_mfma_f32_16x16x32_bf16 v[64:67], v[214:217], v[178:181], v[64:67]
	v_mfma_f32_16x16x32_bf16 v[170:173], v[218:221], v[178:181], v[170:173]
	ds_read_b128 v[178:181], v29
	v_mfma_f32_16x16x32_bf16 v[80:83], v[214:217], v[222:225], v[80:83]
	v_mfma_f32_16x16x32_bf16 v[32:35], v[218:221], v[222:225], v[32:35]
	ds_read_b128 v[222:225], v30
	s_waitcnt lgkmcnt(3)
	v_mfma_f32_16x16x32_bf16 v[88:91], v[158:161], v[226:229], v[88:91]
	v_mfma_f32_16x16x32_bf16 v[92:95], v[162:165], v[226:229], v[92:95]
	v_mfma_f32_16x16x32_bf16 v[96:99], v[214:217], v[226:229], v[96:99]
	v_mfma_f32_16x16x32_bf16 v[36:39], v[218:221], v[226:229], v[36:39]
	ds_read_b128 v[226:229], v31
	s_waitcnt lgkmcnt(3)
	v_mfma_f32_16x16x32_bf16 v[104:107], v[158:161], v[166:169], v[104:107]
	v_mfma_f32_16x16x32_bf16 v[108:111], v[162:165], v[166:169], v[108:111]
	v_mfma_f32_16x16x32_bf16 v[112:115], v[214:217], v[166:169], v[112:115]
	v_mfma_f32_16x16x32_bf16 v[52:55], v[218:221], v[166:169], v[52:55]
	s_waitcnt lgkmcnt(2)
	v_mfma_f32_16x16x32_bf16 v[116:119], v[158:161], v[178:181], v[116:119]
	v_mfma_f32_16x16x32_bf16 v[120:123], v[162:165], v[178:181], v[120:123]
	v_mfma_f32_16x16x32_bf16 v[124:127], v[214:217], v[178:181], v[124:127]
	v_mfma_f32_16x16x32_bf16 v[68:71], v[218:221], v[178:181], v[68:71]
	s_waitcnt lgkmcnt(1)
	v_mfma_f32_16x16x32_bf16 v[128:131], v[158:161], v[222:225], v[128:131]
	v_mfma_f32_16x16x32_bf16 v[132:135], v[162:165], v[222:225], v[132:135]
	v_mfma_f32_16x16x32_bf16 v[136:139], v[214:217], v[222:225], v[136:139]
	v_mfma_f32_16x16x32_bf16 v[84:87], v[218:221], v[222:225], v[84:87]
	s_waitcnt lgkmcnt(0)
	v_mfma_f32_16x16x32_bf16 v[100:103], v[158:161], v[226:229], v[100:103]
	v_mfma_f32_16x16x32_bf16 v[140:143], v[162:165], v[226:229], v[140:143]
	v_mfma_f32_16x16x32_bf16 v[150:153], v[214:217], v[226:229], v[150:153]
	v_mfma_f32_16x16x32_bf16 v[154:157], v[218:221], v[226:229], v[154:157]
	s_add_u32 s46, s0, 0x2b80
	s_addc_u32 s47, s1, 0
	s_add_u32 s48, s14, 0x2b80
	s_waitcnt vmcnt(0)
	s_barrier
	s_addc_u32 s49, s15, 0
	ds_read_b128 v[158:161], v7 offset:32768
	ds_read_b128 v[162:165], v6
	ds_read_b128 v[166:169], v7 offset:34816
	ds_read_b128 v[178:181], v6 offset:2048
	ds_read_b128 v[214:217], v7 offset:36864
	ds_read_b128 v[218:221], v7 offset:38912
	ds_read_b128 v[222:225], v6 offset:4096
	ds_read_b128 v[226:229], v6 offset:6144
	s_waitcnt lgkmcnt(6)
	v_mfma_f32_16x16x32_bf16 v[40:43], v[158:161], v[162:165], v[40:43]
	s_waitcnt lgkmcnt(5)
	v_mfma_f32_16x16x32_bf16 v[44:47], v[166:169], v[162:165], v[44:47]
	s_waitcnt lgkmcnt(4)
	v_mfma_f32_16x16x32_bf16 v[56:59], v[158:161], v[178:181], v[56:59]
	s_mov_b32 m0, s38
	v_mfma_f32_16x16x32_bf16 v[60:63], v[166:169], v[178:181], v[60:63]
	global_load_lds_dwordx4 v0, s[46:47]
	s_waitcnt lgkmcnt(3)
	v_mfma_f32_16x16x32_bf16 v[48:51], v[214:217], v[162:165], v[48:51]
	v_mfma_f32_16x16x32_bf16 v[64:67], v[214:217], v[178:181], v[64:67]
	s_waitcnt lgkmcnt(2)
	v_mfma_f32_16x16x32_bf16 v[174:177], v[218:221], v[162:165], v[174:177]
	ds_read_b128 v[162:165], v6 offset:8192
	v_mfma_f32_16x16x32_bf16 v[170:173], v[218:221], v[178:181], v[170:173]
	ds_read_b128 v[178:181], v6 offset:10240
	s_waitcnt lgkmcnt(3)
	s_mov_b32 m0, s37
	v_mfma_f32_16x16x32_bf16 v[72:75], v[158:161], v[222:225], v[72:75]
	global_load_lds_dwordx4 v0, s[48:49]
	v_mfma_f32_16x16x32_bf16 v[76:79], v[166:169], v[222:225], v[76:79]
	v_mfma_f32_16x16x32_bf16 v[80:83], v[214:217], v[222:225], v[80:83]
	v_mfma_f32_16x16x32_bf16 v[32:35], v[218:221], v[222:225], v[32:35]
	ds_read_b128 v[222:225], v6 offset:12288
	s_waitcnt lgkmcnt(3)
	v_mfma_f32_16x16x32_bf16 v[88:91], v[158:161], v[226:229], v[88:91]
	s_mov_b32 m0, s39
	v_mfma_f32_16x16x32_bf16 v[92:95], v[166:169], v[226:229], v[92:95]
	global_load_lds_dwordx4 v2, s[46:47]
	v_mfma_f32_16x16x32_bf16 v[96:99], v[214:217], v[226:229], v[96:99]
	v_mfma_f32_16x16x32_bf16 v[36:39], v[218:221], v[226:229], v[36:39]
	ds_read_b128 v[226:229], v6 offset:14336
	s_waitcnt lgkmcnt(3)
	v_mfma_f32_16x16x32_bf16 v[104:107], v[158:161], v[162:165], v[104:107]
	s_waitcnt lgkmcnt(2)
	v_mfma_f32_16x16x32_bf16 v[116:119], v[158:161], v[178:181], v[116:119]
	s_waitcnt lgkmcnt(1)
	s_mov_b32 m0, s40
	v_mfma_f32_16x16x32_bf16 v[128:131], v[158:161], v[222:225], v[128:131]
	global_load_lds_dwordx4 v2, s[48:49]
	s_waitcnt lgkmcnt(0)
	v_mfma_f32_16x16x32_bf16 v[100:103], v[158:161], v[226:229], v[100:103]
	ds_read_b128 v[158:161], v7 offset:33792
	v_mfma_f32_16x16x32_bf16 v[108:111], v[166:169], v[162:165], v[108:111]
	v_mfma_f32_16x16x32_bf16 v[120:123], v[166:169], v[178:181], v[120:123]
	v_mfma_f32_16x16x32_bf16 v[132:135], v[166:169], v[222:225], v[132:135]
	s_mov_b32 m0, s41
	v_mfma_f32_16x16x32_bf16 v[140:143], v[166:169], v[226:229], v[140:143]
	global_load_lds_dwordx4 v4, s[46:47]
	ds_read_b128 v[166:169], v6 offset:1024
	v_mfma_f32_16x16x32_bf16 v[112:115], v[214:217], v[162:165], v[112:115]
	v_mfma_f32_16x16x32_bf16 v[52:55], v[218:221], v[162:165], v[52:55]
	ds_read_b128 v[162:165], v7 offset:35840
	v_mfma_f32_16x16x32_bf16 v[124:127], v[214:217], v[178:181], v[124:127]
	v_mfma_f32_16x16x32_bf16 v[68:71], v[218:221], v[178:181], v[68:71]
	ds_read_b128 v[178:181], v6 offset:3072
	s_mov_b32 m0, s42
	v_mfma_f32_16x16x32_bf16 v[136:139], v[214:217], v[222:225], v[136:139]
	global_load_lds_dwordx4 v4, s[48:49]
	v_mfma_f32_16x16x32_bf16 v[84:87], v[218:221], v[222:225], v[84:87]
	ds_read_b128 v[222:225], v6 offset:5120
	v_mfma_f32_16x16x32_bf16 v[150:153], v[214:217], v[226:229], v[150:153]
	ds_read_b128 v[214:217], v7 offset:37888
	v_mfma_f32_16x16x32_bf16 v[154:157], v[218:221], v[226:229], v[154:157]
	ds_read_b128 v[218:221], v7 offset:39936
	ds_read_b128 v[226:229], v6 offset:7168
	s_waitcnt lgkmcnt(6)
	v_mfma_f32_16x16x32_bf16 v[40:43], v[158:161], v[166:169], v[40:43]
	s_waitcnt lgkmcnt(5)
	s_mov_b32 m0, s43
	v_mfma_f32_16x16x32_bf16 v[44:47], v[162:165], v[166:169], v[44:47]
	global_load_lds_dwordx4 v146, s[46:47]
	s_waitcnt lgkmcnt(4)
	v_mfma_f32_16x16x32_bf16 v[56:59], v[158:161], v[178:181], v[56:59]
	v_mfma_f32_16x16x32_bf16 v[60:63], v[162:165], v[178:181], v[60:63]
	s_waitcnt lgkmcnt(3)
	v_mfma_f32_16x16x32_bf16 v[72:75], v[158:161], v[222:225], v[72:75]
	v_mfma_f32_16x16x32_bf16 v[76:79], v[162:165], v[222:225], v[76:79]
	s_waitcnt lgkmcnt(2)
	s_mov_b32 m0, s44
	v_mfma_f32_16x16x32_bf16 v[48:51], v[214:217], v[166:169], v[48:51]
	global_load_lds_dwordx4 v146, s[48:49]
	s_waitcnt lgkmcnt(1)
	v_mfma_f32_16x16x32_bf16 v[174:177], v[218:221], v[166:169], v[174:177]
	ds_read_b128 v[166:169], v6 offset:9216
	v_mfma_f32_16x16x32_bf16 v[64:67], v[214:217], v[178:181], v[64:67]
	v_mfma_f32_16x16x32_bf16 v[170:173], v[218:221], v[178:181], v[170:173]
	ds_read_b128 v[178:181], v6 offset:11264
	v_mfma_f32_16x16x32_bf16 v[80:83], v[214:217], v[222:225], v[80:83]
	v_mfma_f32_16x16x32_bf16 v[32:35], v[218:221], v[222:225], v[32:35]
	ds_read_b128 v[222:225], v6 offset:13312
	s_waitcnt lgkmcnt(3)
	v_mfma_f32_16x16x32_bf16 v[88:91], v[158:161], v[226:229], v[88:91]
	v_mfma_f32_16x16x32_bf16 v[92:95], v[162:165], v[226:229], v[92:95]
	v_mfma_f32_16x16x32_bf16 v[96:99], v[214:217], v[226:229], v[96:99]
	v_mfma_f32_16x16x32_bf16 v[36:39], v[218:221], v[226:229], v[36:39]
	ds_read_b128 v[226:229], v6 offset:15360
	s_waitcnt lgkmcnt(3)
	v_mfma_f32_16x16x32_bf16 v[104:107], v[158:161], v[166:169], v[104:107]
	v_mfma_f32_16x16x32_bf16 v[108:111], v[162:165], v[166:169], v[108:111]
	v_mfma_f32_16x16x32_bf16 v[112:115], v[214:217], v[166:169], v[112:115]
	v_mfma_f32_16x16x32_bf16 v[52:55], v[218:221], v[166:169], v[52:55]
	s_waitcnt lgkmcnt(2)
	v_mfma_f32_16x16x32_bf16 v[116:119], v[158:161], v[178:181], v[116:119]
	v_mfma_f32_16x16x32_bf16 v[120:123], v[162:165], v[178:181], v[120:123]
	v_mfma_f32_16x16x32_bf16 v[124:127], v[214:217], v[178:181], v[124:127]
	v_mfma_f32_16x16x32_bf16 v[68:71], v[218:221], v[178:181], v[68:71]
	s_waitcnt lgkmcnt(1)
	v_mfma_f32_16x16x32_bf16 v[128:131], v[158:161], v[222:225], v[128:131]
	v_mfma_f32_16x16x32_bf16 v[132:135], v[162:165], v[222:225], v[132:135]
	v_mfma_f32_16x16x32_bf16 v[136:139], v[214:217], v[222:225], v[136:139]
	v_mfma_f32_16x16x32_bf16 v[84:87], v[218:221], v[222:225], v[84:87]
	s_waitcnt lgkmcnt(0)
	v_mfma_f32_16x16x32_bf16 v[100:103], v[158:161], v[226:229], v[100:103]
	v_mfma_f32_16x16x32_bf16 v[140:143], v[162:165], v[226:229], v[140:143]
	v_mfma_f32_16x16x32_bf16 v[150:153], v[214:217], v[226:229], v[150:153]
	v_mfma_f32_16x16x32_bf16 v[154:157], v[218:221], v[226:229], v[154:157]
	s_add_u32 s46, s0, 0x2c00
	s_addc_u32 s47, s1, 0
	s_add_u32 s48, s14, 0x2c00
	s_waitcnt vmcnt(0)
	s_barrier
	s_addc_u32 s49, s15, 0
	ds_read_b128 v[158:161], v8
	ds_read_b128 v[162:165], v12
	ds_read_b128 v[166:169], v9
	ds_read_b128 v[178:181], v13
	ds_read_b128 v[214:217], v11
	ds_read_b128 v[218:221], v10
	ds_read_b128 v[222:225], v14
	ds_read_b128 v[226:229], v15
	s_waitcnt lgkmcnt(6)
	v_mfma_f32_16x16x32_bf16 v[40:43], v[158:161], v[162:165], v[40:43]
	s_waitcnt lgkmcnt(5)
	v_mfma_f32_16x16x32_bf16 v[44:47], v[166:169], v[162:165], v[44:47]
	s_waitcnt lgkmcnt(4)
	v_mfma_f32_16x16x32_bf16 v[56:59], v[158:161], v[178:181], v[56:59]
	s_mov_b32 m0, s27
	v_mfma_f32_16x16x32_bf16 v[60:63], v[166:169], v[178:181], v[60:63]
	global_load_lds_dwordx4 v0, s[46:47]
	s_waitcnt lgkmcnt(3)
	v_mfma_f32_16x16x32_bf16 v[48:51], v[214:217], v[162:165], v[48:51]
	v_mfma_f32_16x16x32_bf16 v[64:67], v[214:217], v[178:181], v[64:67]
	s_waitcnt lgkmcnt(2)
	v_mfma_f32_16x16x32_bf16 v[174:177], v[218:221], v[162:165], v[174:177]
	ds_read_b128 v[162:165], v16
	v_mfma_f32_16x16x32_bf16 v[170:173], v[218:221], v[178:181], v[170:173]
	ds_read_b128 v[178:181], v17
	s_waitcnt lgkmcnt(3)
	s_mov_b32 m0, s28
	v_mfma_f32_16x16x32_bf16 v[72:75], v[158:161], v[222:225], v[72:75]
	global_load_lds_dwordx4 v0, s[48:49]
	v_mfma_f32_16x16x32_bf16 v[76:79], v[166:169], v[222:225], v[76:79]
	v_mfma_f32_16x16x32_bf16 v[80:83], v[214:217], v[222:225], v[80:83]
	v_mfma_f32_16x16x32_bf16 v[32:35], v[218:221], v[222:225], v[32:35]
	ds_read_b128 v[222:225], v18
	s_waitcnt lgkmcnt(3)
	v_mfma_f32_16x16x32_bf16 v[88:91], v[158:161], v[226:229], v[88:91]
	s_mov_b32 m0, s29
	v_mfma_f32_16x16x32_bf16 v[92:95], v[166:169], v[226:229], v[92:95]
	global_load_lds_dwordx4 v2, s[46:47]
	v_mfma_f32_16x16x32_bf16 v[96:99], v[214:217], v[226:229], v[96:99]
	v_mfma_f32_16x16x32_bf16 v[36:39], v[218:221], v[226:229], v[36:39]
	ds_read_b128 v[226:229], v19
	s_waitcnt lgkmcnt(3)
	v_mfma_f32_16x16x32_bf16 v[104:107], v[158:161], v[162:165], v[104:107]
	s_waitcnt lgkmcnt(2)
	v_mfma_f32_16x16x32_bf16 v[116:119], v[158:161], v[178:181], v[116:119]
	s_waitcnt lgkmcnt(1)
	s_mov_b32 m0, s30
	v_mfma_f32_16x16x32_bf16 v[128:131], v[158:161], v[222:225], v[128:131]
	global_load_lds_dwordx4 v2, s[48:49]
	s_waitcnt lgkmcnt(0)
	v_mfma_f32_16x16x32_bf16 v[100:103], v[158:161], v[226:229], v[100:103]
	ds_read_b128 v[158:161], v20
	v_mfma_f32_16x16x32_bf16 v[108:111], v[166:169], v[162:165], v[108:111]
	v_mfma_f32_16x16x32_bf16 v[120:123], v[166:169], v[178:181], v[120:123]
	v_mfma_f32_16x16x32_bf16 v[132:135], v[166:169], v[222:225], v[132:135]
	s_mov_b32 m0, s31
	v_mfma_f32_16x16x32_bf16 v[140:143], v[166:169], v[226:229], v[140:143]
	global_load_lds_dwordx4 v4, s[46:47]
	ds_read_b128 v[166:169], v24
	v_mfma_f32_16x16x32_bf16 v[112:115], v[214:217], v[162:165], v[112:115]
	v_mfma_f32_16x16x32_bf16 v[52:55], v[218:221], v[162:165], v[52:55]
	ds_read_b128 v[162:165], v21
	v_mfma_f32_16x16x32_bf16 v[124:127], v[214:217], v[178:181], v[124:127]
	v_mfma_f32_16x16x32_bf16 v[68:71], v[218:221], v[178:181], v[68:71]
	ds_read_b128 v[178:181], v25
	s_mov_b32 m0, s34
	v_mfma_f32_16x16x32_bf16 v[136:139], v[214:217], v[222:225], v[136:139]
	global_load_lds_dwordx4 v4, s[48:49]
	v_mfma_f32_16x16x32_bf16 v[84:87], v[218:221], v[222:225], v[84:87]
	ds_read_b128 v[222:225], v26
	v_mfma_f32_16x16x32_bf16 v[150:153], v[214:217], v[226:229], v[150:153]
	ds_read_b128 v[214:217], v23
	v_mfma_f32_16x16x32_bf16 v[154:157], v[218:221], v[226:229], v[154:157]
	ds_read_b128 v[218:221], v22
	ds_read_b128 v[226:229], v27
	s_waitcnt lgkmcnt(6)
	v_mfma_f32_16x16x32_bf16 v[40:43], v[158:161], v[166:169], v[40:43]
	s_waitcnt lgkmcnt(5)
	s_mov_b32 m0, s35
	v_mfma_f32_16x16x32_bf16 v[44:47], v[162:165], v[166:169], v[44:47]
	global_load_lds_dwordx4 v146, s[46:47]
	s_waitcnt lgkmcnt(4)
	v_mfma_f32_16x16x32_bf16 v[56:59], v[158:161], v[178:181], v[56:59]
	v_mfma_f32_16x16x32_bf16 v[60:63], v[162:165], v[178:181], v[60:63]
	s_waitcnt lgkmcnt(3)
	v_mfma_f32_16x16x32_bf16 v[72:75], v[158:161], v[222:225], v[72:75]
	v_mfma_f32_16x16x32_bf16 v[76:79], v[162:165], v[222:225], v[76:79]
	s_waitcnt lgkmcnt(2)
	s_mov_b32 m0, s36
	v_mfma_f32_16x16x32_bf16 v[48:51], v[214:217], v[166:169], v[48:51]
	global_load_lds_dwordx4 v146, s[48:49]
	s_waitcnt lgkmcnt(1)
	v_mfma_f32_16x16x32_bf16 v[174:177], v[218:221], v[166:169], v[174:177]
	ds_read_b128 v[166:169], v28
	v_mfma_f32_16x16x32_bf16 v[64:67], v[214:217], v[178:181], v[64:67]
	v_mfma_f32_16x16x32_bf16 v[170:173], v[218:221], v[178:181], v[170:173]
	ds_read_b128 v[178:181], v29
	v_mfma_f32_16x16x32_bf16 v[80:83], v[214:217], v[222:225], v[80:83]
	v_mfma_f32_16x16x32_bf16 v[32:35], v[218:221], v[222:225], v[32:35]
	ds_read_b128 v[222:225], v30
	s_waitcnt lgkmcnt(3)
	v_mfma_f32_16x16x32_bf16 v[88:91], v[158:161], v[226:229], v[88:91]
	v_mfma_f32_16x16x32_bf16 v[92:95], v[162:165], v[226:229], v[92:95]
	v_mfma_f32_16x16x32_bf16 v[96:99], v[214:217], v[226:229], v[96:99]
	v_mfma_f32_16x16x32_bf16 v[36:39], v[218:221], v[226:229], v[36:39]
	ds_read_b128 v[226:229], v31
	s_waitcnt lgkmcnt(3)
	v_mfma_f32_16x16x32_bf16 v[104:107], v[158:161], v[166:169], v[104:107]
	v_mfma_f32_16x16x32_bf16 v[108:111], v[162:165], v[166:169], v[108:111]
	v_mfma_f32_16x16x32_bf16 v[112:115], v[214:217], v[166:169], v[112:115]
	v_mfma_f32_16x16x32_bf16 v[52:55], v[218:221], v[166:169], v[52:55]
	s_waitcnt lgkmcnt(2)
	v_mfma_f32_16x16x32_bf16 v[116:119], v[158:161], v[178:181], v[116:119]
	v_mfma_f32_16x16x32_bf16 v[120:123], v[162:165], v[178:181], v[120:123]
	v_mfma_f32_16x16x32_bf16 v[124:127], v[214:217], v[178:181], v[124:127]
	v_mfma_f32_16x16x32_bf16 v[68:71], v[218:221], v[178:181], v[68:71]
	s_waitcnt lgkmcnt(1)
	v_mfma_f32_16x16x32_bf16 v[128:131], v[158:161], v[222:225], v[128:131]
	v_mfma_f32_16x16x32_bf16 v[132:135], v[162:165], v[222:225], v[132:135]
	v_mfma_f32_16x16x32_bf16 v[136:139], v[214:217], v[222:225], v[136:139]
	v_mfma_f32_16x16x32_bf16 v[84:87], v[218:221], v[222:225], v[84:87]
	s_waitcnt lgkmcnt(0)
	v_mfma_f32_16x16x32_bf16 v[100:103], v[158:161], v[226:229], v[100:103]
	v_mfma_f32_16x16x32_bf16 v[140:143], v[162:165], v[226:229], v[140:143]
	v_mfma_f32_16x16x32_bf16 v[150:153], v[214:217], v[226:229], v[150:153]
	v_mfma_f32_16x16x32_bf16 v[154:157], v[218:221], v[226:229], v[154:157]
	s_add_u32 s46, s0, 0x2c80
	s_addc_u32 s47, s1, 0
	s_add_u32 s48, s14, 0x2c80
	s_waitcnt vmcnt(0)
	s_barrier
	s_addc_u32 s49, s15, 0
	ds_read_b128 v[158:161], v7 offset:32768
	ds_read_b128 v[162:165], v6
	ds_read_b128 v[166:169], v7 offset:34816
	ds_read_b128 v[178:181], v6 offset:2048
	ds_read_b128 v[214:217], v7 offset:36864
	ds_read_b128 v[218:221], v7 offset:38912
	ds_read_b128 v[222:225], v6 offset:4096
	ds_read_b128 v[226:229], v6 offset:6144
	s_waitcnt lgkmcnt(6)
	v_mfma_f32_16x16x32_bf16 v[40:43], v[158:161], v[162:165], v[40:43]
	s_waitcnt lgkmcnt(5)
	v_mfma_f32_16x16x32_bf16 v[44:47], v[166:169], v[162:165], v[44:47]
	s_waitcnt lgkmcnt(4)
	v_mfma_f32_16x16x32_bf16 v[56:59], v[158:161], v[178:181], v[56:59]
	s_mov_b32 m0, s38
	v_mfma_f32_16x16x32_bf16 v[60:63], v[166:169], v[178:181], v[60:63]
	global_load_lds_dwordx4 v0, s[46:47]
	s_waitcnt lgkmcnt(3)
	v_mfma_f32_16x16x32_bf16 v[48:51], v[214:217], v[162:165], v[48:51]
	v_mfma_f32_16x16x32_bf16 v[64:67], v[214:217], v[178:181], v[64:67]
	s_waitcnt lgkmcnt(2)
	v_mfma_f32_16x16x32_bf16 v[174:177], v[218:221], v[162:165], v[174:177]
	ds_read_b128 v[162:165], v6 offset:8192
	v_mfma_f32_16x16x32_bf16 v[170:173], v[218:221], v[178:181], v[170:173]
	ds_read_b128 v[178:181], v6 offset:10240
	s_waitcnt lgkmcnt(3)
	s_mov_b32 m0, s37
	v_mfma_f32_16x16x32_bf16 v[72:75], v[158:161], v[222:225], v[72:75]
	global_load_lds_dwordx4 v0, s[48:49]
	v_mfma_f32_16x16x32_bf16 v[76:79], v[166:169], v[222:225], v[76:79]
	v_mfma_f32_16x16x32_bf16 v[80:83], v[214:217], v[222:225], v[80:83]
	v_mfma_f32_16x16x32_bf16 v[32:35], v[218:221], v[222:225], v[32:35]
	ds_read_b128 v[222:225], v6 offset:12288
	s_waitcnt lgkmcnt(3)
	v_mfma_f32_16x16x32_bf16 v[88:91], v[158:161], v[226:229], v[88:91]
	s_mov_b32 m0, s39
	v_mfma_f32_16x16x32_bf16 v[92:95], v[166:169], v[226:229], v[92:95]
	global_load_lds_dwordx4 v2, s[46:47]
	v_mfma_f32_16x16x32_bf16 v[96:99], v[214:217], v[226:229], v[96:99]
	v_mfma_f32_16x16x32_bf16 v[36:39], v[218:221], v[226:229], v[36:39]
	ds_read_b128 v[226:229], v6 offset:14336
	s_waitcnt lgkmcnt(3)
	v_mfma_f32_16x16x32_bf16 v[104:107], v[158:161], v[162:165], v[104:107]
	s_waitcnt lgkmcnt(2)
	v_mfma_f32_16x16x32_bf16 v[116:119], v[158:161], v[178:181], v[116:119]
	s_waitcnt lgkmcnt(1)
	s_mov_b32 m0, s40
	v_mfma_f32_16x16x32_bf16 v[128:131], v[158:161], v[222:225], v[128:131]
	global_load_lds_dwordx4 v2, s[48:49]
	s_waitcnt lgkmcnt(0)
	v_mfma_f32_16x16x32_bf16 v[100:103], v[158:161], v[226:229], v[100:103]
	ds_read_b128 v[158:161], v7 offset:33792
	v_mfma_f32_16x16x32_bf16 v[108:111], v[166:169], v[162:165], v[108:111]
	v_mfma_f32_16x16x32_bf16 v[120:123], v[166:169], v[178:181], v[120:123]
	v_mfma_f32_16x16x32_bf16 v[132:135], v[166:169], v[222:225], v[132:135]
	s_mov_b32 m0, s41
	v_mfma_f32_16x16x32_bf16 v[140:143], v[166:169], v[226:229], v[140:143]
	global_load_lds_dwordx4 v4, s[46:47]
	ds_read_b128 v[166:169], v6 offset:1024
	v_mfma_f32_16x16x32_bf16 v[112:115], v[214:217], v[162:165], v[112:115]
	v_mfma_f32_16x16x32_bf16 v[52:55], v[218:221], v[162:165], v[52:55]
	ds_read_b128 v[162:165], v7 offset:35840
	v_mfma_f32_16x16x32_bf16 v[124:127], v[214:217], v[178:181], v[124:127]
	v_mfma_f32_16x16x32_bf16 v[68:71], v[218:221], v[178:181], v[68:71]
	ds_read_b128 v[178:181], v6 offset:3072
	s_mov_b32 m0, s42
	v_mfma_f32_16x16x32_bf16 v[136:139], v[214:217], v[222:225], v[136:139]
	global_load_lds_dwordx4 v4, s[48:49]
	v_mfma_f32_16x16x32_bf16 v[84:87], v[218:221], v[222:225], v[84:87]
	ds_read_b128 v[222:225], v6 offset:5120
	v_mfma_f32_16x16x32_bf16 v[150:153], v[214:217], v[226:229], v[150:153]
	ds_read_b128 v[214:217], v7 offset:37888
	v_mfma_f32_16x16x32_bf16 v[154:157], v[218:221], v[226:229], v[154:157]
	ds_read_b128 v[218:221], v7 offset:39936
	ds_read_b128 v[226:229], v6 offset:7168
	s_waitcnt lgkmcnt(6)
	v_mfma_f32_16x16x32_bf16 v[40:43], v[158:161], v[166:169], v[40:43]
	s_waitcnt lgkmcnt(5)
	s_mov_b32 m0, s43
	v_mfma_f32_16x16x32_bf16 v[44:47], v[162:165], v[166:169], v[44:47]
	global_load_lds_dwordx4 v146, s[46:47]
	s_waitcnt lgkmcnt(4)
	v_mfma_f32_16x16x32_bf16 v[56:59], v[158:161], v[178:181], v[56:59]
	v_mfma_f32_16x16x32_bf16 v[60:63], v[162:165], v[178:181], v[60:63]
	s_waitcnt lgkmcnt(3)
	v_mfma_f32_16x16x32_bf16 v[72:75], v[158:161], v[222:225], v[72:75]
	v_mfma_f32_16x16x32_bf16 v[76:79], v[162:165], v[222:225], v[76:79]
	s_waitcnt lgkmcnt(2)
	s_mov_b32 m0, s44
	v_mfma_f32_16x16x32_bf16 v[48:51], v[214:217], v[166:169], v[48:51]
	global_load_lds_dwordx4 v146, s[48:49]
	s_waitcnt lgkmcnt(1)
	v_mfma_f32_16x16x32_bf16 v[174:177], v[218:221], v[166:169], v[174:177]
	ds_read_b128 v[166:169], v6 offset:9216
	v_mfma_f32_16x16x32_bf16 v[64:67], v[214:217], v[178:181], v[64:67]
	v_mfma_f32_16x16x32_bf16 v[170:173], v[218:221], v[178:181], v[170:173]
	ds_read_b128 v[178:181], v6 offset:11264
	v_mfma_f32_16x16x32_bf16 v[80:83], v[214:217], v[222:225], v[80:83]
	v_mfma_f32_16x16x32_bf16 v[32:35], v[218:221], v[222:225], v[32:35]
	ds_read_b128 v[222:225], v6 offset:13312
	s_waitcnt lgkmcnt(3)
	v_mfma_f32_16x16x32_bf16 v[88:91], v[158:161], v[226:229], v[88:91]
	v_mfma_f32_16x16x32_bf16 v[92:95], v[162:165], v[226:229], v[92:95]
	v_mfma_f32_16x16x32_bf16 v[96:99], v[214:217], v[226:229], v[96:99]
	v_mfma_f32_16x16x32_bf16 v[36:39], v[218:221], v[226:229], v[36:39]
	ds_read_b128 v[226:229], v6 offset:15360
	s_waitcnt lgkmcnt(3)
	v_mfma_f32_16x16x32_bf16 v[104:107], v[158:161], v[166:169], v[104:107]
	v_mfma_f32_16x16x32_bf16 v[108:111], v[162:165], v[166:169], v[108:111]
	v_mfma_f32_16x16x32_bf16 v[112:115], v[214:217], v[166:169], v[112:115]
	v_mfma_f32_16x16x32_bf16 v[52:55], v[218:221], v[166:169], v[52:55]
	s_waitcnt lgkmcnt(2)
	v_mfma_f32_16x16x32_bf16 v[116:119], v[158:161], v[178:181], v[116:119]
	v_mfma_f32_16x16x32_bf16 v[120:123], v[162:165], v[178:181], v[120:123]
	v_mfma_f32_16x16x32_bf16 v[124:127], v[214:217], v[178:181], v[124:127]
	v_mfma_f32_16x16x32_bf16 v[68:71], v[218:221], v[178:181], v[68:71]
	s_waitcnt lgkmcnt(1)
	v_mfma_f32_16x16x32_bf16 v[128:131], v[158:161], v[222:225], v[128:131]
	v_mfma_f32_16x16x32_bf16 v[132:135], v[162:165], v[222:225], v[132:135]
	v_mfma_f32_16x16x32_bf16 v[136:139], v[214:217], v[222:225], v[136:139]
	v_mfma_f32_16x16x32_bf16 v[84:87], v[218:221], v[222:225], v[84:87]
	s_waitcnt lgkmcnt(0)
	v_mfma_f32_16x16x32_bf16 v[100:103], v[158:161], v[226:229], v[100:103]
	v_mfma_f32_16x16x32_bf16 v[140:143], v[162:165], v[226:229], v[140:143]
	v_mfma_f32_16x16x32_bf16 v[150:153], v[214:217], v[226:229], v[150:153]
	v_mfma_f32_16x16x32_bf16 v[154:157], v[218:221], v[226:229], v[154:157]
	s_add_u32 s46, s0, 0x2d00
	s_addc_u32 s47, s1, 0
	s_add_u32 s48, s14, 0x2d00
	s_waitcnt vmcnt(0)
	s_barrier
	s_addc_u32 s49, s15, 0
	ds_read_b128 v[158:161], v8
	ds_read_b128 v[162:165], v12
	ds_read_b128 v[166:169], v9
	ds_read_b128 v[178:181], v13
	ds_read_b128 v[214:217], v11
	ds_read_b128 v[218:221], v10
	ds_read_b128 v[222:225], v14
	ds_read_b128 v[226:229], v15
	s_waitcnt lgkmcnt(6)
	v_mfma_f32_16x16x32_bf16 v[40:43], v[158:161], v[162:165], v[40:43]
	s_waitcnt lgkmcnt(5)
	v_mfma_f32_16x16x32_bf16 v[44:47], v[166:169], v[162:165], v[44:47]
	s_waitcnt lgkmcnt(4)
	v_mfma_f32_16x16x32_bf16 v[56:59], v[158:161], v[178:181], v[56:59]
	s_mov_b32 m0, s27
	v_mfma_f32_16x16x32_bf16 v[60:63], v[166:169], v[178:181], v[60:63]
	global_load_lds_dwordx4 v0, s[46:47]
	s_waitcnt lgkmcnt(3)
	v_mfma_f32_16x16x32_bf16 v[48:51], v[214:217], v[162:165], v[48:51]
	v_mfma_f32_16x16x32_bf16 v[64:67], v[214:217], v[178:181], v[64:67]
	s_waitcnt lgkmcnt(2)
	v_mfma_f32_16x16x32_bf16 v[174:177], v[218:221], v[162:165], v[174:177]
	ds_read_b128 v[162:165], v16
	v_mfma_f32_16x16x32_bf16 v[170:173], v[218:221], v[178:181], v[170:173]
	ds_read_b128 v[178:181], v17
	s_waitcnt lgkmcnt(3)
	s_mov_b32 m0, s28
	v_mfma_f32_16x16x32_bf16 v[72:75], v[158:161], v[222:225], v[72:75]
	global_load_lds_dwordx4 v0, s[48:49]
	v_mfma_f32_16x16x32_bf16 v[76:79], v[166:169], v[222:225], v[76:79]
	v_mfma_f32_16x16x32_bf16 v[80:83], v[214:217], v[222:225], v[80:83]
	v_mfma_f32_16x16x32_bf16 v[32:35], v[218:221], v[222:225], v[32:35]
	ds_read_b128 v[222:225], v18
	s_waitcnt lgkmcnt(3)
	v_mfma_f32_16x16x32_bf16 v[88:91], v[158:161], v[226:229], v[88:91]
	s_mov_b32 m0, s29
	v_mfma_f32_16x16x32_bf16 v[92:95], v[166:169], v[226:229], v[92:95]
	global_load_lds_dwordx4 v2, s[46:47]
	v_mfma_f32_16x16x32_bf16 v[96:99], v[214:217], v[226:229], v[96:99]
	v_mfma_f32_16x16x32_bf16 v[36:39], v[218:221], v[226:229], v[36:39]
	ds_read_b128 v[226:229], v19
	s_waitcnt lgkmcnt(3)
	v_mfma_f32_16x16x32_bf16 v[104:107], v[158:161], v[162:165], v[104:107]
	s_waitcnt lgkmcnt(2)
	v_mfma_f32_16x16x32_bf16 v[116:119], v[158:161], v[178:181], v[116:119]
	s_waitcnt lgkmcnt(1)
	s_mov_b32 m0, s30
	v_mfma_f32_16x16x32_bf16 v[128:131], v[158:161], v[222:225], v[128:131]
	global_load_lds_dwordx4 v2, s[48:49]
	s_waitcnt lgkmcnt(0)
	v_mfma_f32_16x16x32_bf16 v[100:103], v[158:161], v[226:229], v[100:103]
	ds_read_b128 v[158:161], v20
	v_mfma_f32_16x16x32_bf16 v[108:111], v[166:169], v[162:165], v[108:111]
	v_mfma_f32_16x16x32_bf16 v[120:123], v[166:169], v[178:181], v[120:123]
	v_mfma_f32_16x16x32_bf16 v[132:135], v[166:169], v[222:225], v[132:135]
	s_mov_b32 m0, s31
	v_mfma_f32_16x16x32_bf16 v[140:143], v[166:169], v[226:229], v[140:143]
	global_load_lds_dwordx4 v4, s[46:47]
	ds_read_b128 v[166:169], v24
	v_mfma_f32_16x16x32_bf16 v[112:115], v[214:217], v[162:165], v[112:115]
	v_mfma_f32_16x16x32_bf16 v[52:55], v[218:221], v[162:165], v[52:55]
	ds_read_b128 v[162:165], v21
	v_mfma_f32_16x16x32_bf16 v[124:127], v[214:217], v[178:181], v[124:127]
	v_mfma_f32_16x16x32_bf16 v[68:71], v[218:221], v[178:181], v[68:71]
	ds_read_b128 v[178:181], v25
	s_mov_b32 m0, s34
	v_mfma_f32_16x16x32_bf16 v[136:139], v[214:217], v[222:225], v[136:139]
	global_load_lds_dwordx4 v4, s[48:49]
	v_mfma_f32_16x16x32_bf16 v[84:87], v[218:221], v[222:225], v[84:87]
	ds_read_b128 v[222:225], v26
	v_mfma_f32_16x16x32_bf16 v[150:153], v[214:217], v[226:229], v[150:153]
	ds_read_b128 v[214:217], v23
	v_mfma_f32_16x16x32_bf16 v[154:157], v[218:221], v[226:229], v[154:157]
	ds_read_b128 v[218:221], v22
	ds_read_b128 v[226:229], v27
	s_waitcnt lgkmcnt(6)
	v_mfma_f32_16x16x32_bf16 v[40:43], v[158:161], v[166:169], v[40:43]
	s_waitcnt lgkmcnt(5)
	s_mov_b32 m0, s35
	v_mfma_f32_16x16x32_bf16 v[44:47], v[162:165], v[166:169], v[44:47]
	global_load_lds_dwordx4 v146, s[46:47]
	s_waitcnt lgkmcnt(4)
	v_mfma_f32_16x16x32_bf16 v[56:59], v[158:161], v[178:181], v[56:59]
	v_mfma_f32_16x16x32_bf16 v[60:63], v[162:165], v[178:181], v[60:63]
	s_waitcnt lgkmcnt(3)
	v_mfma_f32_16x16x32_bf16 v[72:75], v[158:161], v[222:225], v[72:75]
	v_mfma_f32_16x16x32_bf16 v[76:79], v[162:165], v[222:225], v[76:79]
	s_waitcnt lgkmcnt(2)
	s_mov_b32 m0, s36
	v_mfma_f32_16x16x32_bf16 v[48:51], v[214:217], v[166:169], v[48:51]
	global_load_lds_dwordx4 v146, s[48:49]
	s_waitcnt lgkmcnt(1)
	v_mfma_f32_16x16x32_bf16 v[174:177], v[218:221], v[166:169], v[174:177]
	ds_read_b128 v[166:169], v28
	v_mfma_f32_16x16x32_bf16 v[64:67], v[214:217], v[178:181], v[64:67]
	v_mfma_f32_16x16x32_bf16 v[170:173], v[218:221], v[178:181], v[170:173]
	ds_read_b128 v[178:181], v29
	v_mfma_f32_16x16x32_bf16 v[80:83], v[214:217], v[222:225], v[80:83]
	v_mfma_f32_16x16x32_bf16 v[32:35], v[218:221], v[222:225], v[32:35]
	ds_read_b128 v[222:225], v30
	s_waitcnt lgkmcnt(3)
	v_mfma_f32_16x16x32_bf16 v[88:91], v[158:161], v[226:229], v[88:91]
	v_mfma_f32_16x16x32_bf16 v[92:95], v[162:165], v[226:229], v[92:95]
	v_mfma_f32_16x16x32_bf16 v[96:99], v[214:217], v[226:229], v[96:99]
	v_mfma_f32_16x16x32_bf16 v[36:39], v[218:221], v[226:229], v[36:39]
	ds_read_b128 v[226:229], v31
	s_waitcnt lgkmcnt(3)
	v_mfma_f32_16x16x32_bf16 v[104:107], v[158:161], v[166:169], v[104:107]
	v_mfma_f32_16x16x32_bf16 v[108:111], v[162:165], v[166:169], v[108:111]
	v_mfma_f32_16x16x32_bf16 v[112:115], v[214:217], v[166:169], v[112:115]
	v_mfma_f32_16x16x32_bf16 v[52:55], v[218:221], v[166:169], v[52:55]
	s_waitcnt lgkmcnt(2)
	v_mfma_f32_16x16x32_bf16 v[116:119], v[158:161], v[178:181], v[116:119]
	v_mfma_f32_16x16x32_bf16 v[120:123], v[162:165], v[178:181], v[120:123]
	v_mfma_f32_16x16x32_bf16 v[124:127], v[214:217], v[178:181], v[124:127]
	v_mfma_f32_16x16x32_bf16 v[68:71], v[218:221], v[178:181], v[68:71]
	s_waitcnt lgkmcnt(1)
	v_mfma_f32_16x16x32_bf16 v[128:131], v[158:161], v[222:225], v[128:131]
	v_mfma_f32_16x16x32_bf16 v[132:135], v[162:165], v[222:225], v[132:135]
	v_mfma_f32_16x16x32_bf16 v[136:139], v[214:217], v[222:225], v[136:139]
	v_mfma_f32_16x16x32_bf16 v[84:87], v[218:221], v[222:225], v[84:87]
	s_waitcnt lgkmcnt(0)
	v_mfma_f32_16x16x32_bf16 v[100:103], v[158:161], v[226:229], v[100:103]
	v_mfma_f32_16x16x32_bf16 v[140:143], v[162:165], v[226:229], v[140:143]
	v_mfma_f32_16x16x32_bf16 v[150:153], v[214:217], v[226:229], v[150:153]
	v_mfma_f32_16x16x32_bf16 v[154:157], v[218:221], v[226:229], v[154:157]
	s_add_u32 s46, s0, 0x2d80
	s_addc_u32 s47, s1, 0
	s_add_u32 s48, s14, 0x2d80
	s_waitcnt vmcnt(0)
	s_barrier
	s_addc_u32 s49, s15, 0
	ds_read_b128 v[158:161], v7 offset:32768
	ds_read_b128 v[162:165], v6
	ds_read_b128 v[166:169], v7 offset:34816
	ds_read_b128 v[178:181], v6 offset:2048
	ds_read_b128 v[214:217], v7 offset:36864
	ds_read_b128 v[218:221], v7 offset:38912
	ds_read_b128 v[222:225], v6 offset:4096
	ds_read_b128 v[226:229], v6 offset:6144
	s_waitcnt lgkmcnt(6)
	v_mfma_f32_16x16x32_bf16 v[40:43], v[158:161], v[162:165], v[40:43]
	s_waitcnt lgkmcnt(5)
	v_mfma_f32_16x16x32_bf16 v[44:47], v[166:169], v[162:165], v[44:47]
	s_waitcnt lgkmcnt(4)
	v_mfma_f32_16x16x32_bf16 v[56:59], v[158:161], v[178:181], v[56:59]
	s_mov_b32 m0, s38
	v_mfma_f32_16x16x32_bf16 v[60:63], v[166:169], v[178:181], v[60:63]
	global_load_lds_dwordx4 v0, s[46:47]
	s_waitcnt lgkmcnt(3)
	v_mfma_f32_16x16x32_bf16 v[48:51], v[214:217], v[162:165], v[48:51]
	v_mfma_f32_16x16x32_bf16 v[64:67], v[214:217], v[178:181], v[64:67]
	s_waitcnt lgkmcnt(2)
	v_mfma_f32_16x16x32_bf16 v[174:177], v[218:221], v[162:165], v[174:177]
	ds_read_b128 v[162:165], v6 offset:8192
	v_mfma_f32_16x16x32_bf16 v[170:173], v[218:221], v[178:181], v[170:173]
	ds_read_b128 v[178:181], v6 offset:10240
	s_waitcnt lgkmcnt(3)
	s_mov_b32 m0, s37
	v_mfma_f32_16x16x32_bf16 v[72:75], v[158:161], v[222:225], v[72:75]
	global_load_lds_dwordx4 v0, s[48:49]
	v_mfma_f32_16x16x32_bf16 v[76:79], v[166:169], v[222:225], v[76:79]
	v_mfma_f32_16x16x32_bf16 v[80:83], v[214:217], v[222:225], v[80:83]
	v_mfma_f32_16x16x32_bf16 v[32:35], v[218:221], v[222:225], v[32:35]
	ds_read_b128 v[222:225], v6 offset:12288
	s_waitcnt lgkmcnt(3)
	v_mfma_f32_16x16x32_bf16 v[88:91], v[158:161], v[226:229], v[88:91]
	s_mov_b32 m0, s39
	v_mfma_f32_16x16x32_bf16 v[92:95], v[166:169], v[226:229], v[92:95]
	global_load_lds_dwordx4 v2, s[46:47]
	v_mfma_f32_16x16x32_bf16 v[96:99], v[214:217], v[226:229], v[96:99]
	v_mfma_f32_16x16x32_bf16 v[36:39], v[218:221], v[226:229], v[36:39]
	ds_read_b128 v[226:229], v6 offset:14336
	s_waitcnt lgkmcnt(3)
	v_mfma_f32_16x16x32_bf16 v[104:107], v[158:161], v[162:165], v[104:107]
	s_waitcnt lgkmcnt(2)
	v_mfma_f32_16x16x32_bf16 v[116:119], v[158:161], v[178:181], v[116:119]
	s_waitcnt lgkmcnt(1)
	s_mov_b32 m0, s40
	v_mfma_f32_16x16x32_bf16 v[128:131], v[158:161], v[222:225], v[128:131]
	global_load_lds_dwordx4 v2, s[48:49]
	s_waitcnt lgkmcnt(0)
	v_mfma_f32_16x16x32_bf16 v[100:103], v[158:161], v[226:229], v[100:103]
	ds_read_b128 v[158:161], v7 offset:33792
	v_mfma_f32_16x16x32_bf16 v[108:111], v[166:169], v[162:165], v[108:111]
	v_mfma_f32_16x16x32_bf16 v[120:123], v[166:169], v[178:181], v[120:123]
	v_mfma_f32_16x16x32_bf16 v[132:135], v[166:169], v[222:225], v[132:135]
	s_mov_b32 m0, s41
	v_mfma_f32_16x16x32_bf16 v[140:143], v[166:169], v[226:229], v[140:143]
	global_load_lds_dwordx4 v4, s[46:47]
	ds_read_b128 v[166:169], v6 offset:1024
	v_mfma_f32_16x16x32_bf16 v[112:115], v[214:217], v[162:165], v[112:115]
	v_mfma_f32_16x16x32_bf16 v[52:55], v[218:221], v[162:165], v[52:55]
	ds_read_b128 v[162:165], v7 offset:35840
	v_mfma_f32_16x16x32_bf16 v[124:127], v[214:217], v[178:181], v[124:127]
	v_mfma_f32_16x16x32_bf16 v[68:71], v[218:221], v[178:181], v[68:71]
	ds_read_b128 v[178:181], v6 offset:3072
	s_mov_b32 m0, s42
	v_mfma_f32_16x16x32_bf16 v[136:139], v[214:217], v[222:225], v[136:139]
	global_load_lds_dwordx4 v4, s[48:49]
	v_mfma_f32_16x16x32_bf16 v[84:87], v[218:221], v[222:225], v[84:87]
	ds_read_b128 v[222:225], v6 offset:5120
	v_mfma_f32_16x16x32_bf16 v[150:153], v[214:217], v[226:229], v[150:153]
	ds_read_b128 v[214:217], v7 offset:37888
	v_mfma_f32_16x16x32_bf16 v[154:157], v[218:221], v[226:229], v[154:157]
	ds_read_b128 v[218:221], v7 offset:39936
	ds_read_b128 v[226:229], v6 offset:7168
	s_waitcnt lgkmcnt(6)
	v_mfma_f32_16x16x32_bf16 v[40:43], v[158:161], v[166:169], v[40:43]
	s_waitcnt lgkmcnt(5)
	s_mov_b32 m0, s43
	v_mfma_f32_16x16x32_bf16 v[44:47], v[162:165], v[166:169], v[44:47]
	global_load_lds_dwordx4 v146, s[46:47]
	s_waitcnt lgkmcnt(4)
	v_mfma_f32_16x16x32_bf16 v[56:59], v[158:161], v[178:181], v[56:59]
	v_mfma_f32_16x16x32_bf16 v[60:63], v[162:165], v[178:181], v[60:63]
	s_waitcnt lgkmcnt(3)
	v_mfma_f32_16x16x32_bf16 v[72:75], v[158:161], v[222:225], v[72:75]
	v_mfma_f32_16x16x32_bf16 v[76:79], v[162:165], v[222:225], v[76:79]
	s_waitcnt lgkmcnt(2)
	s_mov_b32 m0, s44
	v_mfma_f32_16x16x32_bf16 v[48:51], v[214:217], v[166:169], v[48:51]
	global_load_lds_dwordx4 v146, s[48:49]
	s_waitcnt lgkmcnt(1)
	v_mfma_f32_16x16x32_bf16 v[174:177], v[218:221], v[166:169], v[174:177]
	ds_read_b128 v[166:169], v6 offset:9216
	v_mfma_f32_16x16x32_bf16 v[64:67], v[214:217], v[178:181], v[64:67]
	v_mfma_f32_16x16x32_bf16 v[170:173], v[218:221], v[178:181], v[170:173]
	ds_read_b128 v[178:181], v6 offset:11264
	v_mfma_f32_16x16x32_bf16 v[80:83], v[214:217], v[222:225], v[80:83]
	v_mfma_f32_16x16x32_bf16 v[32:35], v[218:221], v[222:225], v[32:35]
	ds_read_b128 v[222:225], v6 offset:13312
	s_waitcnt lgkmcnt(3)
	v_mfma_f32_16x16x32_bf16 v[88:91], v[158:161], v[226:229], v[88:91]
	v_mfma_f32_16x16x32_bf16 v[92:95], v[162:165], v[226:229], v[92:95]
	v_mfma_f32_16x16x32_bf16 v[96:99], v[214:217], v[226:229], v[96:99]
	v_mfma_f32_16x16x32_bf16 v[36:39], v[218:221], v[226:229], v[36:39]
	ds_read_b128 v[226:229], v6 offset:15360
	s_waitcnt lgkmcnt(3)
	v_mfma_f32_16x16x32_bf16 v[104:107], v[158:161], v[166:169], v[104:107]
	v_mfma_f32_16x16x32_bf16 v[108:111], v[162:165], v[166:169], v[108:111]
	v_mfma_f32_16x16x32_bf16 v[112:115], v[214:217], v[166:169], v[112:115]
	v_mfma_f32_16x16x32_bf16 v[52:55], v[218:221], v[166:169], v[52:55]
	s_waitcnt lgkmcnt(2)
	v_mfma_f32_16x16x32_bf16 v[116:119], v[158:161], v[178:181], v[116:119]
	v_mfma_f32_16x16x32_bf16 v[120:123], v[162:165], v[178:181], v[120:123]
	v_mfma_f32_16x16x32_bf16 v[124:127], v[214:217], v[178:181], v[124:127]
	v_mfma_f32_16x16x32_bf16 v[68:71], v[218:221], v[178:181], v[68:71]
	s_waitcnt lgkmcnt(1)
	v_mfma_f32_16x16x32_bf16 v[128:131], v[158:161], v[222:225], v[128:131]
	v_mfma_f32_16x16x32_bf16 v[132:135], v[162:165], v[222:225], v[132:135]
	v_mfma_f32_16x16x32_bf16 v[136:139], v[214:217], v[222:225], v[136:139]
	v_mfma_f32_16x16x32_bf16 v[84:87], v[218:221], v[222:225], v[84:87]
	s_waitcnt lgkmcnt(0)
	v_mfma_f32_16x16x32_bf16 v[100:103], v[158:161], v[226:229], v[100:103]
	v_mfma_f32_16x16x32_bf16 v[140:143], v[162:165], v[226:229], v[140:143]
	v_mfma_f32_16x16x32_bf16 v[150:153], v[214:217], v[226:229], v[150:153]
	v_mfma_f32_16x16x32_bf16 v[154:157], v[218:221], v[226:229], v[154:157]
	s_add_u32 s46, s0, 0x2e00
	s_addc_u32 s47, s1, 0
	s_add_u32 s48, s14, 0x2e00
	s_waitcnt vmcnt(0)
	s_barrier
	s_addc_u32 s49, s15, 0
	ds_read_b128 v[158:161], v8
	ds_read_b128 v[162:165], v12
	ds_read_b128 v[166:169], v9
	ds_read_b128 v[178:181], v13
	ds_read_b128 v[214:217], v11
	ds_read_b128 v[218:221], v10
	ds_read_b128 v[222:225], v14
	ds_read_b128 v[226:229], v15
	s_waitcnt lgkmcnt(6)
	v_mfma_f32_16x16x32_bf16 v[40:43], v[158:161], v[162:165], v[40:43]
	s_waitcnt lgkmcnt(5)
	v_mfma_f32_16x16x32_bf16 v[44:47], v[166:169], v[162:165], v[44:47]
	s_waitcnt lgkmcnt(4)
	v_mfma_f32_16x16x32_bf16 v[56:59], v[158:161], v[178:181], v[56:59]
	s_mov_b32 m0, s27
	v_mfma_f32_16x16x32_bf16 v[60:63], v[166:169], v[178:181], v[60:63]
	global_load_lds_dwordx4 v0, s[46:47]
	s_waitcnt lgkmcnt(3)
	v_mfma_f32_16x16x32_bf16 v[48:51], v[214:217], v[162:165], v[48:51]
	v_mfma_f32_16x16x32_bf16 v[64:67], v[214:217], v[178:181], v[64:67]
	s_waitcnt lgkmcnt(2)
	v_mfma_f32_16x16x32_bf16 v[174:177], v[218:221], v[162:165], v[174:177]
	ds_read_b128 v[162:165], v16
	v_mfma_f32_16x16x32_bf16 v[170:173], v[218:221], v[178:181], v[170:173]
	ds_read_b128 v[178:181], v17
	s_waitcnt lgkmcnt(3)
	s_mov_b32 m0, s28
	v_mfma_f32_16x16x32_bf16 v[72:75], v[158:161], v[222:225], v[72:75]
	global_load_lds_dwordx4 v0, s[48:49]
	v_mfma_f32_16x16x32_bf16 v[76:79], v[166:169], v[222:225], v[76:79]
	v_mfma_f32_16x16x32_bf16 v[80:83], v[214:217], v[222:225], v[80:83]
	v_mfma_f32_16x16x32_bf16 v[32:35], v[218:221], v[222:225], v[32:35]
	ds_read_b128 v[222:225], v18
	s_waitcnt lgkmcnt(3)
	v_mfma_f32_16x16x32_bf16 v[88:91], v[158:161], v[226:229], v[88:91]
	s_mov_b32 m0, s29
	v_mfma_f32_16x16x32_bf16 v[92:95], v[166:169], v[226:229], v[92:95]
	global_load_lds_dwordx4 v2, s[46:47]
	v_mfma_f32_16x16x32_bf16 v[96:99], v[214:217], v[226:229], v[96:99]
	v_mfma_f32_16x16x32_bf16 v[36:39], v[218:221], v[226:229], v[36:39]
	ds_read_b128 v[226:229], v19
	s_waitcnt lgkmcnt(3)
	v_mfma_f32_16x16x32_bf16 v[104:107], v[158:161], v[162:165], v[104:107]
	s_waitcnt lgkmcnt(2)
	v_mfma_f32_16x16x32_bf16 v[116:119], v[158:161], v[178:181], v[116:119]
	s_waitcnt lgkmcnt(1)
	s_mov_b32 m0, s30
	v_mfma_f32_16x16x32_bf16 v[128:131], v[158:161], v[222:225], v[128:131]
	global_load_lds_dwordx4 v2, s[48:49]
	s_waitcnt lgkmcnt(0)
	v_mfma_f32_16x16x32_bf16 v[100:103], v[158:161], v[226:229], v[100:103]
	ds_read_b128 v[158:161], v20
	v_mfma_f32_16x16x32_bf16 v[108:111], v[166:169], v[162:165], v[108:111]
	v_mfma_f32_16x16x32_bf16 v[120:123], v[166:169], v[178:181], v[120:123]
	v_mfma_f32_16x16x32_bf16 v[132:135], v[166:169], v[222:225], v[132:135]
	s_mov_b32 m0, s31
	v_mfma_f32_16x16x32_bf16 v[140:143], v[166:169], v[226:229], v[140:143]
	global_load_lds_dwordx4 v4, s[46:47]
	ds_read_b128 v[166:169], v24
	v_mfma_f32_16x16x32_bf16 v[112:115], v[214:217], v[162:165], v[112:115]
	v_mfma_f32_16x16x32_bf16 v[52:55], v[218:221], v[162:165], v[52:55]
	ds_read_b128 v[162:165], v21
	v_mfma_f32_16x16x32_bf16 v[124:127], v[214:217], v[178:181], v[124:127]
	v_mfma_f32_16x16x32_bf16 v[68:71], v[218:221], v[178:181], v[68:71]
	ds_read_b128 v[178:181], v25
	s_mov_b32 m0, s34
	v_mfma_f32_16x16x32_bf16 v[136:139], v[214:217], v[222:225], v[136:139]
	global_load_lds_dwordx4 v4, s[48:49]
	v_mfma_f32_16x16x32_bf16 v[84:87], v[218:221], v[222:225], v[84:87]
	ds_read_b128 v[222:225], v26
	v_mfma_f32_16x16x32_bf16 v[150:153], v[214:217], v[226:229], v[150:153]
	ds_read_b128 v[214:217], v23
	v_mfma_f32_16x16x32_bf16 v[154:157], v[218:221], v[226:229], v[154:157]
	ds_read_b128 v[218:221], v22
	ds_read_b128 v[226:229], v27
	s_waitcnt lgkmcnt(6)
	v_mfma_f32_16x16x32_bf16 v[40:43], v[158:161], v[166:169], v[40:43]
	s_waitcnt lgkmcnt(5)
	s_mov_b32 m0, s35
	v_mfma_f32_16x16x32_bf16 v[44:47], v[162:165], v[166:169], v[44:47]
	global_load_lds_dwordx4 v146, s[46:47]
	s_waitcnt lgkmcnt(4)
	v_mfma_f32_16x16x32_bf16 v[56:59], v[158:161], v[178:181], v[56:59]
	v_mfma_f32_16x16x32_bf16 v[60:63], v[162:165], v[178:181], v[60:63]
	s_waitcnt lgkmcnt(3)
	v_mfma_f32_16x16x32_bf16 v[72:75], v[158:161], v[222:225], v[72:75]
	v_mfma_f32_16x16x32_bf16 v[76:79], v[162:165], v[222:225], v[76:79]
	s_waitcnt lgkmcnt(2)
	s_mov_b32 m0, s36
	v_mfma_f32_16x16x32_bf16 v[48:51], v[214:217], v[166:169], v[48:51]
	global_load_lds_dwordx4 v146, s[48:49]
	s_waitcnt lgkmcnt(1)
	v_mfma_f32_16x16x32_bf16 v[174:177], v[218:221], v[166:169], v[174:177]
	ds_read_b128 v[166:169], v28
	v_mfma_f32_16x16x32_bf16 v[64:67], v[214:217], v[178:181], v[64:67]
	v_mfma_f32_16x16x32_bf16 v[170:173], v[218:221], v[178:181], v[170:173]
	ds_read_b128 v[178:181], v29
	v_mfma_f32_16x16x32_bf16 v[80:83], v[214:217], v[222:225], v[80:83]
	v_mfma_f32_16x16x32_bf16 v[32:35], v[218:221], v[222:225], v[32:35]
	ds_read_b128 v[222:225], v30
	s_waitcnt lgkmcnt(3)
	v_mfma_f32_16x16x32_bf16 v[88:91], v[158:161], v[226:229], v[88:91]
	v_mfma_f32_16x16x32_bf16 v[92:95], v[162:165], v[226:229], v[92:95]
	v_mfma_f32_16x16x32_bf16 v[96:99], v[214:217], v[226:229], v[96:99]
	v_mfma_f32_16x16x32_bf16 v[36:39], v[218:221], v[226:229], v[36:39]
	ds_read_b128 v[226:229], v31
	s_waitcnt lgkmcnt(3)
	v_mfma_f32_16x16x32_bf16 v[104:107], v[158:161], v[166:169], v[104:107]
	v_mfma_f32_16x16x32_bf16 v[108:111], v[162:165], v[166:169], v[108:111]
	v_mfma_f32_16x16x32_bf16 v[112:115], v[214:217], v[166:169], v[112:115]
	v_mfma_f32_16x16x32_bf16 v[52:55], v[218:221], v[166:169], v[52:55]
	s_waitcnt lgkmcnt(2)
	v_mfma_f32_16x16x32_bf16 v[116:119], v[158:161], v[178:181], v[116:119]
	v_mfma_f32_16x16x32_bf16 v[120:123], v[162:165], v[178:181], v[120:123]
	v_mfma_f32_16x16x32_bf16 v[124:127], v[214:217], v[178:181], v[124:127]
	v_mfma_f32_16x16x32_bf16 v[68:71], v[218:221], v[178:181], v[68:71]
	s_waitcnt lgkmcnt(1)
	v_mfma_f32_16x16x32_bf16 v[128:131], v[158:161], v[222:225], v[128:131]
	v_mfma_f32_16x16x32_bf16 v[132:135], v[162:165], v[222:225], v[132:135]
	v_mfma_f32_16x16x32_bf16 v[136:139], v[214:217], v[222:225], v[136:139]
	v_mfma_f32_16x16x32_bf16 v[84:87], v[218:221], v[222:225], v[84:87]
	s_waitcnt lgkmcnt(0)
	v_mfma_f32_16x16x32_bf16 v[100:103], v[158:161], v[226:229], v[100:103]
	v_mfma_f32_16x16x32_bf16 v[140:143], v[162:165], v[226:229], v[140:143]
	v_mfma_f32_16x16x32_bf16 v[150:153], v[214:217], v[226:229], v[150:153]
	v_mfma_f32_16x16x32_bf16 v[154:157], v[218:221], v[226:229], v[154:157]
	s_add_u32 s46, s0, 0x2e80
	s_addc_u32 s47, s1, 0
	s_add_u32 s48, s14, 0x2e80
	s_waitcnt vmcnt(0)
	s_barrier
	s_addc_u32 s49, s15, 0
	ds_read_b128 v[158:161], v7 offset:32768
	ds_read_b128 v[162:165], v6
	ds_read_b128 v[166:169], v7 offset:34816
	ds_read_b128 v[178:181], v6 offset:2048
	ds_read_b128 v[214:217], v7 offset:36864
	ds_read_b128 v[218:221], v7 offset:38912
	ds_read_b128 v[222:225], v6 offset:4096
	ds_read_b128 v[226:229], v6 offset:6144
	s_waitcnt lgkmcnt(6)
	v_mfma_f32_16x16x32_bf16 v[40:43], v[158:161], v[162:165], v[40:43]
	s_waitcnt lgkmcnt(5)
	v_mfma_f32_16x16x32_bf16 v[44:47], v[166:169], v[162:165], v[44:47]
	s_waitcnt lgkmcnt(4)
	v_mfma_f32_16x16x32_bf16 v[56:59], v[158:161], v[178:181], v[56:59]
	s_mov_b32 m0, s38
	v_mfma_f32_16x16x32_bf16 v[60:63], v[166:169], v[178:181], v[60:63]
	global_load_lds_dwordx4 v0, s[46:47]
	s_waitcnt lgkmcnt(3)
	v_mfma_f32_16x16x32_bf16 v[48:51], v[214:217], v[162:165], v[48:51]
	v_mfma_f32_16x16x32_bf16 v[64:67], v[214:217], v[178:181], v[64:67]
	s_waitcnt lgkmcnt(2)
	v_mfma_f32_16x16x32_bf16 v[174:177], v[218:221], v[162:165], v[174:177]
	ds_read_b128 v[162:165], v6 offset:8192
	v_mfma_f32_16x16x32_bf16 v[170:173], v[218:221], v[178:181], v[170:173]
	ds_read_b128 v[178:181], v6 offset:10240
	s_waitcnt lgkmcnt(3)
	s_mov_b32 m0, s37
	v_mfma_f32_16x16x32_bf16 v[72:75], v[158:161], v[222:225], v[72:75]
	global_load_lds_dwordx4 v0, s[48:49]
	v_mfma_f32_16x16x32_bf16 v[76:79], v[166:169], v[222:225], v[76:79]
	v_mfma_f32_16x16x32_bf16 v[80:83], v[214:217], v[222:225], v[80:83]
	v_mfma_f32_16x16x32_bf16 v[32:35], v[218:221], v[222:225], v[32:35]
	ds_read_b128 v[222:225], v6 offset:12288
	s_waitcnt lgkmcnt(3)
	v_mfma_f32_16x16x32_bf16 v[88:91], v[158:161], v[226:229], v[88:91]
	s_mov_b32 m0, s39
	v_mfma_f32_16x16x32_bf16 v[92:95], v[166:169], v[226:229], v[92:95]
	global_load_lds_dwordx4 v2, s[46:47]
	v_mfma_f32_16x16x32_bf16 v[96:99], v[214:217], v[226:229], v[96:99]
	v_mfma_f32_16x16x32_bf16 v[36:39], v[218:221], v[226:229], v[36:39]
	ds_read_b128 v[226:229], v6 offset:14336
	s_waitcnt lgkmcnt(3)
	v_mfma_f32_16x16x32_bf16 v[104:107], v[158:161], v[162:165], v[104:107]
	s_waitcnt lgkmcnt(2)
	v_mfma_f32_16x16x32_bf16 v[116:119], v[158:161], v[178:181], v[116:119]
	s_waitcnt lgkmcnt(1)
	s_mov_b32 m0, s40
	v_mfma_f32_16x16x32_bf16 v[128:131], v[158:161], v[222:225], v[128:131]
	global_load_lds_dwordx4 v2, s[48:49]
	s_waitcnt lgkmcnt(0)
	v_mfma_f32_16x16x32_bf16 v[100:103], v[158:161], v[226:229], v[100:103]
	ds_read_b128 v[158:161], v7 offset:33792
	v_mfma_f32_16x16x32_bf16 v[108:111], v[166:169], v[162:165], v[108:111]
	v_mfma_f32_16x16x32_bf16 v[120:123], v[166:169], v[178:181], v[120:123]
	v_mfma_f32_16x16x32_bf16 v[132:135], v[166:169], v[222:225], v[132:135]
	s_mov_b32 m0, s41
	v_mfma_f32_16x16x32_bf16 v[140:143], v[166:169], v[226:229], v[140:143]
	global_load_lds_dwordx4 v4, s[46:47]
	ds_read_b128 v[166:169], v6 offset:1024
	v_mfma_f32_16x16x32_bf16 v[112:115], v[214:217], v[162:165], v[112:115]
	v_mfma_f32_16x16x32_bf16 v[52:55], v[218:221], v[162:165], v[52:55]
	ds_read_b128 v[162:165], v7 offset:35840
	v_mfma_f32_16x16x32_bf16 v[124:127], v[214:217], v[178:181], v[124:127]
	v_mfma_f32_16x16x32_bf16 v[68:71], v[218:221], v[178:181], v[68:71]
	ds_read_b128 v[178:181], v6 offset:3072
	s_mov_b32 m0, s42
	v_mfma_f32_16x16x32_bf16 v[136:139], v[214:217], v[222:225], v[136:139]
	global_load_lds_dwordx4 v4, s[48:49]
	v_mfma_f32_16x16x32_bf16 v[84:87], v[218:221], v[222:225], v[84:87]
	ds_read_b128 v[222:225], v6 offset:5120
	v_mfma_f32_16x16x32_bf16 v[150:153], v[214:217], v[226:229], v[150:153]
	ds_read_b128 v[214:217], v7 offset:37888
	v_mfma_f32_16x16x32_bf16 v[154:157], v[218:221], v[226:229], v[154:157]
	ds_read_b128 v[218:221], v7 offset:39936
	ds_read_b128 v[226:229], v6 offset:7168
	s_waitcnt lgkmcnt(6)
	v_mfma_f32_16x16x32_bf16 v[40:43], v[158:161], v[166:169], v[40:43]
	s_waitcnt lgkmcnt(5)
	s_mov_b32 m0, s43
	v_mfma_f32_16x16x32_bf16 v[44:47], v[162:165], v[166:169], v[44:47]
	global_load_lds_dwordx4 v146, s[46:47]
	s_waitcnt lgkmcnt(4)
	v_mfma_f32_16x16x32_bf16 v[56:59], v[158:161], v[178:181], v[56:59]
	v_mfma_f32_16x16x32_bf16 v[60:63], v[162:165], v[178:181], v[60:63]
	s_waitcnt lgkmcnt(3)
	v_mfma_f32_16x16x32_bf16 v[72:75], v[158:161], v[222:225], v[72:75]
	v_mfma_f32_16x16x32_bf16 v[76:79], v[162:165], v[222:225], v[76:79]
	s_waitcnt lgkmcnt(2)
	s_mov_b32 m0, s44
	v_mfma_f32_16x16x32_bf16 v[48:51], v[214:217], v[166:169], v[48:51]
	global_load_lds_dwordx4 v146, s[48:49]
	s_waitcnt lgkmcnt(1)
	v_mfma_f32_16x16x32_bf16 v[174:177], v[218:221], v[166:169], v[174:177]
	ds_read_b128 v[166:169], v6 offset:9216
	v_mfma_f32_16x16x32_bf16 v[64:67], v[214:217], v[178:181], v[64:67]
	v_mfma_f32_16x16x32_bf16 v[170:173], v[218:221], v[178:181], v[170:173]
	ds_read_b128 v[178:181], v6 offset:11264
	v_mfma_f32_16x16x32_bf16 v[80:83], v[214:217], v[222:225], v[80:83]
	v_mfma_f32_16x16x32_bf16 v[32:35], v[218:221], v[222:225], v[32:35]
	ds_read_b128 v[222:225], v6 offset:13312
	s_waitcnt lgkmcnt(3)
	v_mfma_f32_16x16x32_bf16 v[88:91], v[158:161], v[226:229], v[88:91]
	v_mfma_f32_16x16x32_bf16 v[92:95], v[162:165], v[226:229], v[92:95]
	v_mfma_f32_16x16x32_bf16 v[96:99], v[214:217], v[226:229], v[96:99]
	v_mfma_f32_16x16x32_bf16 v[36:39], v[218:221], v[226:229], v[36:39]
	ds_read_b128 v[226:229], v6 offset:15360
	s_waitcnt lgkmcnt(3)
	v_mfma_f32_16x16x32_bf16 v[104:107], v[158:161], v[166:169], v[104:107]
	v_mfma_f32_16x16x32_bf16 v[108:111], v[162:165], v[166:169], v[108:111]
	v_mfma_f32_16x16x32_bf16 v[112:115], v[214:217], v[166:169], v[112:115]
	v_mfma_f32_16x16x32_bf16 v[52:55], v[218:221], v[166:169], v[52:55]
	s_waitcnt lgkmcnt(2)
	v_mfma_f32_16x16x32_bf16 v[116:119], v[158:161], v[178:181], v[116:119]
	v_mfma_f32_16x16x32_bf16 v[120:123], v[162:165], v[178:181], v[120:123]
	v_mfma_f32_16x16x32_bf16 v[124:127], v[214:217], v[178:181], v[124:127]
	v_mfma_f32_16x16x32_bf16 v[68:71], v[218:221], v[178:181], v[68:71]
	s_waitcnt lgkmcnt(1)
	v_mfma_f32_16x16x32_bf16 v[128:131], v[158:161], v[222:225], v[128:131]
	v_mfma_f32_16x16x32_bf16 v[132:135], v[162:165], v[222:225], v[132:135]
	v_mfma_f32_16x16x32_bf16 v[136:139], v[214:217], v[222:225], v[136:139]
	v_mfma_f32_16x16x32_bf16 v[84:87], v[218:221], v[222:225], v[84:87]
	s_waitcnt lgkmcnt(0)
	v_mfma_f32_16x16x32_bf16 v[100:103], v[158:161], v[226:229], v[100:103]
	v_mfma_f32_16x16x32_bf16 v[140:143], v[162:165], v[226:229], v[140:143]
	v_mfma_f32_16x16x32_bf16 v[150:153], v[214:217], v[226:229], v[150:153]
	v_mfma_f32_16x16x32_bf16 v[154:157], v[218:221], v[226:229], v[154:157]
	s_add_u32 s46, s0, 0x2f00
	s_addc_u32 s47, s1, 0
	s_add_u32 s48, s14, 0x2f00
	s_waitcnt vmcnt(0)
	s_barrier
	s_addc_u32 s49, s15, 0
	v_lshl_add_u64 v[158:159], s[46:47], 0, v[0:1]
	s_mov_b32 s45, m0
	s_mov_b32 m0, s27
	s_nop 0
	global_load_lds_dwordx4 v[158:159], off
	s_mov_b32 m0, s45
	v_lshl_add_u64 v[158:159], s[48:49], 0, v[0:1]
	s_mov_b32 s45, m0
	s_mov_b32 m0, s28
	s_nop 0
	global_load_lds_dwordx4 v[158:159], off
	s_mov_b32 m0, s45
	v_lshl_add_u64 v[158:159], s[46:47], 0, v[2:3]
	s_mov_b32 s45, m0
	s_mov_b32 m0, s29
	s_nop 0
	global_load_lds_dwordx4 v[158:159], off
	s_mov_b32 m0, s45
	v_lshl_add_u64 v[158:159], s[48:49], 0, v[2:3]
	s_mov_b32 s45, m0
	s_mov_b32 m0, s30
	s_nop 0
	global_load_lds_dwordx4 v[158:159], off
	s_mov_b32 m0, s45
	v_lshl_add_u64 v[158:159], s[46:47], 0, v[4:5]
	s_mov_b32 s45, m0
	s_mov_b32 m0, s31
	s_nop 0
	global_load_lds_dwordx4 v[158:159], off
	s_mov_b32 m0, s45
	v_lshl_add_u64 v[158:159], s[48:49], 0, v[4:5]
	s_mov_b32 s45, m0
	s_mov_b32 m0, s34
	s_nop 0
	global_load_lds_dwordx4 v[158:159], off
	s_mov_b32 m0, s45
	v_lshl_add_u64 v[158:159], s[46:47], 0, v[146:147]
	s_mov_b32 s45, m0
	s_mov_b32 m0, s35
	s_nop 0
	global_load_lds_dwordx4 v[158:159], off
	s_mov_b32 m0, s45
	v_lshl_add_u64 v[158:159], s[48:49], 0, v[146:147]
	s_mov_b32 s45, m0
	s_mov_b32 m0, s36
	s_nop 0
	global_load_lds_dwordx4 v[158:159], off
	s_mov_b32 m0, s45
	ds_read_b128 v[158:161], v8
	ds_read_b128 v[162:165], v9
	ds_read_b128 v[166:169], v11
	ds_read_b128 v[214:217], v10
	ds_read_b128 v[178:181], v12
	ds_read_b128 v[218:221], v13
	ds_read_b128 v[222:225], v14
	ds_read_b128 v[226:229], v15
	s_waitcnt lgkmcnt(3)
	v_mfma_f32_16x16x32_bf16 v[40:43], v[158:161], v[178:181], v[40:43]
	v_mfma_f32_16x16x32_bf16 v[44:47], v[162:165], v[178:181], v[44:47]
	v_mfma_f32_16x16x32_bf16 v[48:51], v[166:169], v[178:181], v[48:51]
	v_mfma_f32_16x16x32_bf16 v[174:177], v[214:217], v[178:181], v[174:177]
	ds_read_b128 v[178:181], v16
	s_waitcnt lgkmcnt(3)
	v_mfma_f32_16x16x32_bf16 v[56:59], v[158:161], v[218:221], v[56:59]
	v_mfma_f32_16x16x32_bf16 v[60:63], v[162:165], v[218:221], v[60:63]
	v_mfma_f32_16x16x32_bf16 v[64:67], v[166:169], v[218:221], v[64:67]
	v_mfma_f32_16x16x32_bf16 v[170:173], v[214:217], v[218:221], v[170:173]
	ds_read_b128 v[218:221], v17
	s_waitcnt lgkmcnt(3)
	v_mfma_f32_16x16x32_bf16 v[72:75], v[158:161], v[222:225], v[72:75]
	v_mfma_f32_16x16x32_bf16 v[76:79], v[162:165], v[222:225], v[76:79]
	v_mfma_f32_16x16x32_bf16 v[80:83], v[166:169], v[222:225], v[80:83]
	v_mfma_f32_16x16x32_bf16 v[32:35], v[214:217], v[222:225], v[32:35]
	ds_read_b128 v[222:225], v18
	s_waitcnt lgkmcnt(3)
	v_mfma_f32_16x16x32_bf16 v[88:91], v[158:161], v[226:229], v[88:91]
	v_mfma_f32_16x16x32_bf16 v[92:95], v[162:165], v[226:229], v[92:95]
	v_mfma_f32_16x16x32_bf16 v[96:99], v[166:169], v[226:229], v[96:99]
	v_mfma_f32_16x16x32_bf16 v[36:39], v[214:217], v[226:229], v[36:39]
	ds_read_b128 v[226:229], v19
	s_waitcnt lgkmcnt(3)
	v_mfma_f32_16x16x32_bf16 v[104:107], v[158:161], v[178:181], v[104:107]
	v_mfma_f32_16x16x32_bf16 v[108:111], v[162:165], v[178:181], v[108:111]
	v_mfma_f32_16x16x32_bf16 v[112:115], v[166:169], v[178:181], v[112:115]
	v_mfma_f32_16x16x32_bf16 v[52:55], v[214:217], v[178:181], v[52:55]
	s_waitcnt lgkmcnt(2)
	v_mfma_f32_16x16x32_bf16 v[116:119], v[158:161], v[218:221], v[116:119]
	v_mfma_f32_16x16x32_bf16 v[120:123], v[162:165], v[218:221], v[120:123]
	v_mfma_f32_16x16x32_bf16 v[124:127], v[166:169], v[218:221], v[124:127]
	v_mfma_f32_16x16x32_bf16 v[68:71], v[214:217], v[218:221], v[68:71]
	s_waitcnt lgkmcnt(1)
	v_mfma_f32_16x16x32_bf16 v[132:135], v[162:165], v[222:225], v[132:135]
	v_mfma_f32_16x16x32_bf16 v[84:87], v[214:217], v[222:225], v[84:87]
	s_waitcnt lgkmcnt(0)
	v_mfma_f32_16x16x32_bf16 v[100:103], v[158:161], v[226:229], v[100:103]
	v_mfma_f32_16x16x32_bf16 v[150:153], v[166:169], v[226:229], v[150:153]
	v_mfma_f32_16x16x32_bf16 v[154:157], v[214:217], v[226:229], v[154:157]
	v_mfma_f32_16x16x32_bf16 v[128:131], v[158:161], v[222:225], v[128:131]
	v_mfma_f32_16x16x32_bf16 v[136:139], v[166:169], v[222:225], v[136:139]
	v_mfma_f32_16x16x32_bf16 v[140:143], v[162:165], v[226:229], v[140:143]
	ds_read_b128 v[158:161], v20
	ds_read_b128 v[162:165], v21
	ds_read_b128 v[166:169], v23
	ds_read_b128 v[214:217], v22
	ds_read_b128 v[178:181], v24
	ds_read_b128 v[218:221], v25
	ds_read_b128 v[222:225], v26
	ds_read_b128 v[226:229], v27
	s_waitcnt lgkmcnt(3)
	v_mfma_f32_16x16x32_bf16 v[40:43], v[158:161], v[178:181], v[40:43]
	v_mfma_f32_16x16x32_bf16 v[44:47], v[162:165], v[178:181], v[44:47]
	v_mfma_f32_16x16x32_bf16 v[48:51], v[166:169], v[178:181], v[48:51]
	v_mfma_f32_16x16x32_bf16 v[174:177], v[214:217], v[178:181], v[174:177]
	ds_read_b128 v[178:181], v28
	s_waitcnt lgkmcnt(3)
	v_mfma_f32_16x16x32_bf16 v[56:59], v[158:161], v[218:221], v[56:59]
	v_mfma_f32_16x16x32_bf16 v[60:63], v[162:165], v[218:221], v[60:63]
	v_mfma_f32_16x16x32_bf16 v[64:67], v[166:169], v[218:221], v[64:67]
	v_mfma_f32_16x16x32_bf16 v[170:173], v[214:217], v[218:221], v[170:173]
	ds_read_b128 v[218:221], v29
	s_waitcnt lgkmcnt(3)
	v_mfma_f32_16x16x32_bf16 v[72:75], v[158:161], v[222:225], v[72:75]
	v_mfma_f32_16x16x32_bf16 v[76:79], v[162:165], v[222:225], v[76:79]
	v_mfma_f32_16x16x32_bf16 v[80:83], v[166:169], v[222:225], v[80:83]
	v_mfma_f32_16x16x32_bf16 v[32:35], v[214:217], v[222:225], v[32:35]
	ds_read_b128 v[222:225], v30
	s_waitcnt lgkmcnt(3)
	v_mfma_f32_16x16x32_bf16 v[88:91], v[158:161], v[226:229], v[88:91]
	v_mfma_f32_16x16x32_bf16 v[92:95], v[162:165], v[226:229], v[92:95]
	v_mfma_f32_16x16x32_bf16 v[96:99], v[166:169], v[226:229], v[96:99]
	v_mfma_f32_16x16x32_bf16 v[36:39], v[214:217], v[226:229], v[36:39]
	ds_read_b128 v[226:229], v31
	s_waitcnt lgkmcnt(3)
	v_mfma_f32_16x16x32_bf16 v[104:107], v[158:161], v[178:181], v[104:107]
	v_mfma_f32_16x16x32_bf16 v[108:111], v[162:165], v[178:181], v[108:111]
	v_mfma_f32_16x16x32_bf16 v[112:115], v[166:169], v[178:181], v[112:115]
	v_mfma_f32_16x16x32_bf16 v[52:55], v[214:217], v[178:181], v[52:55]
	s_waitcnt lgkmcnt(2)
	v_mfma_f32_16x16x32_bf16 v[116:119], v[158:161], v[218:221], v[116:119]
	v_mfma_f32_16x16x32_bf16 v[120:123], v[162:165], v[218:221], v[120:123]
	v_mfma_f32_16x16x32_bf16 v[124:127], v[166:169], v[218:221], v[124:127]
	v_mfma_f32_16x16x32_bf16 v[68:71], v[214:217], v[218:221], v[68:71]
	s_waitcnt lgkmcnt(1)
	v_mfma_f32_16x16x32_bf16 v[132:135], v[162:165], v[222:225], v[132:135]
	v_mfma_f32_16x16x32_bf16 v[84:87], v[214:217], v[222:225], v[84:87]
	s_waitcnt lgkmcnt(0)
	v_mfma_f32_16x16x32_bf16 v[100:103], v[158:161], v[226:229], v[100:103]
	v_mfma_f32_16x16x32_bf16 v[150:153], v[166:169], v[226:229], v[150:153]
	v_mfma_f32_16x16x32_bf16 v[154:157], v[214:217], v[226:229], v[154:157]
	v_mfma_f32_16x16x32_bf16 v[128:131], v[158:161], v[222:225], v[128:131]
	v_mfma_f32_16x16x32_bf16 v[136:139], v[166:169], v[222:225], v[136:139]
	v_mfma_f32_16x16x32_bf16 v[140:143], v[162:165], v[226:229], v[140:143]
	s_add_u32 s0, s0, 0x2f80
	s_addc_u32 s1, s1, 0
	s_add_u32 s14, s14, 0x2f80
	s_waitcnt vmcnt(0)
	s_barrier
	s_addc_u32 s15, s15, 0
	v_lshl_add_u64 v[158:159], s[0:1], 0, v[0:1]
	s_mov_b32 s45, m0
	s_mov_b32 m0, s38
	s_nop 0
	global_load_lds_dwordx4 v[158:159], off
	s_mov_b32 m0, s45
	v_lshl_add_u64 v[158:159], s[14:15], 0, v[0:1]
	s_mov_b32 s38, m0
	s_mov_b32 m0, s37
	s_nop 0
	global_load_lds_dwordx4 v[158:159], off
	s_mov_b32 m0, s38
	v_lshl_add_u64 v[158:159], s[0:1], 0, v[2:3]
	s_mov_b32 s37, m0
	s_mov_b32 m0, s39
	s_nop 0
	global_load_lds_dwordx4 v[158:159], off
	s_mov_b32 m0, s37
	v_lshl_add_u64 v[158:159], s[14:15], 0, v[2:3]
	s_mov_b32 s37, m0
	s_mov_b32 m0, s40
	s_nop 0
	global_load_lds_dwordx4 v[158:159], off
	s_mov_b32 m0, s37
	v_lshl_add_u64 v[158:159], s[0:1], 0, v[4:5]
	s_mov_b32 s37, m0
	s_mov_b32 m0, s41
	s_nop 0
	global_load_lds_dwordx4 v[158:159], off
	s_mov_b32 m0, s37
	v_lshl_add_u64 v[158:159], s[14:15], 0, v[4:5]
	s_mov_b32 s37, m0
	s_mov_b32 m0, s42
	s_nop 0
	global_load_lds_dwordx4 v[158:159], off
	s_mov_b32 m0, s37
	v_lshl_add_u64 v[158:159], s[0:1], 0, v[146:147]
	s_mov_b32 s0, m0
	s_mov_b32 m0, s43
	s_nop 0
	global_load_lds_dwordx4 v[158:159], off
	s_mov_b32 m0, s0
	v_lshl_add_u64 v[158:159], s[14:15], 0, v[146:147]
	s_mov_b32 s0, m0
	s_mov_b32 m0, s44
	s_nop 0
	global_load_lds_dwordx4 v[158:159], off
	s_mov_b32 m0, s0
	ds_read_b128 v[158:161], v7 offset:32768
	ds_read_b128 v[162:165], v7 offset:34816
	ds_read_b128 v[166:169], v7 offset:36864
	ds_read_b128 v[214:217], v7 offset:38912
	ds_read_b128 v[178:181], v6
	ds_read_b128 v[218:221], v6 offset:2048
	ds_read_b128 v[222:225], v6 offset:4096
	ds_read_b128 v[226:229], v6 offset:6144
	s_waitcnt lgkmcnt(3)
	v_mfma_f32_16x16x32_bf16 v[40:43], v[158:161], v[178:181], v[40:43]
	v_mfma_f32_16x16x32_bf16 v[44:47], v[162:165], v[178:181], v[44:47]
	v_mfma_f32_16x16x32_bf16 v[48:51], v[166:169], v[178:181], v[48:51]
	v_mfma_f32_16x16x32_bf16 v[174:177], v[214:217], v[178:181], v[174:177]
	ds_read_b128 v[178:181], v6 offset:8192
	s_waitcnt lgkmcnt(3)
	v_mfma_f32_16x16x32_bf16 v[56:59], v[158:161], v[218:221], v[56:59]
	v_mfma_f32_16x16x32_bf16 v[60:63], v[162:165], v[218:221], v[60:63]
	v_mfma_f32_16x16x32_bf16 v[64:67], v[166:169], v[218:221], v[64:67]
	v_mfma_f32_16x16x32_bf16 v[170:173], v[214:217], v[218:221], v[170:173]
	ds_read_b128 v[218:221], v6 offset:10240
	s_waitcnt lgkmcnt(3)
	v_mfma_f32_16x16x32_bf16 v[72:75], v[158:161], v[222:225], v[72:75]
	v_mfma_f32_16x16x32_bf16 v[76:79], v[162:165], v[222:225], v[76:79]
	v_mfma_f32_16x16x32_bf16 v[80:83], v[166:169], v[222:225], v[80:83]
	v_mfma_f32_16x16x32_bf16 v[32:35], v[214:217], v[222:225], v[32:35]
	ds_read_b128 v[222:225], v6 offset:12288
	s_waitcnt lgkmcnt(3)
	v_mfma_f32_16x16x32_bf16 v[88:91], v[158:161], v[226:229], v[88:91]
	v_mfma_f32_16x16x32_bf16 v[92:95], v[162:165], v[226:229], v[92:95]
	v_mfma_f32_16x16x32_bf16 v[96:99], v[166:169], v[226:229], v[96:99]
	v_mfma_f32_16x16x32_bf16 v[36:39], v[214:217], v[226:229], v[36:39]
	ds_read_b128 v[226:229], v6 offset:14336
	s_waitcnt lgkmcnt(3)
	v_mfma_f32_16x16x32_bf16 v[104:107], v[158:161], v[178:181], v[104:107]
	v_mfma_f32_16x16x32_bf16 v[108:111], v[162:165], v[178:181], v[108:111]
	v_mfma_f32_16x16x32_bf16 v[112:115], v[166:169], v[178:181], v[112:115]
	v_mfma_f32_16x16x32_bf16 v[52:55], v[214:217], v[178:181], v[52:55]
	s_waitcnt lgkmcnt(2)
	v_mfma_f32_16x16x32_bf16 v[116:119], v[158:161], v[218:221], v[116:119]
	v_mfma_f32_16x16x32_bf16 v[120:123], v[162:165], v[218:221], v[120:123]
	v_mfma_f32_16x16x32_bf16 v[124:127], v[166:169], v[218:221], v[124:127]
	v_mfma_f32_16x16x32_bf16 v[68:71], v[214:217], v[218:221], v[68:71]
	s_waitcnt lgkmcnt(1)
	v_mfma_f32_16x16x32_bf16 v[132:135], v[162:165], v[222:225], v[132:135]
	v_mfma_f32_16x16x32_bf16 v[84:87], v[214:217], v[222:225], v[84:87]
	s_waitcnt lgkmcnt(0)
	v_mfma_f32_16x16x32_bf16 v[100:103], v[158:161], v[226:229], v[100:103]
	v_mfma_f32_16x16x32_bf16 v[150:153], v[166:169], v[226:229], v[150:153]
	v_mfma_f32_16x16x32_bf16 v[154:157], v[214:217], v[226:229], v[154:157]
	v_mfma_f32_16x16x32_bf16 v[128:131], v[158:161], v[222:225], v[128:131]
	v_mfma_f32_16x16x32_bf16 v[136:139], v[166:169], v[222:225], v[136:139]
	v_mfma_f32_16x16x32_bf16 v[140:143], v[162:165], v[226:229], v[140:143]
	ds_read_b128 v[158:161], v7 offset:33792
	ds_read_b128 v[162:165], v7 offset:35840
	ds_read_b128 v[166:169], v7 offset:37888
	ds_read_b128 v[214:217], v7 offset:39936
	ds_read_b128 v[178:181], v6 offset:1024
	ds_read_b128 v[218:221], v6 offset:3072
	ds_read_b128 v[222:225], v6 offset:5120
	ds_read_b128 v[226:229], v6 offset:7168
	s_waitcnt lgkmcnt(3)
	v_mfma_f32_16x16x32_bf16 v[40:43], v[158:161], v[178:181], v[40:43]
	v_mfma_f32_16x16x32_bf16 v[44:47], v[162:165], v[178:181], v[44:47]
	v_mfma_f32_16x16x32_bf16 v[48:51], v[166:169], v[178:181], v[48:51]
	v_mfma_f32_16x16x32_bf16 v[174:177], v[214:217], v[178:181], v[174:177]
	ds_read_b128 v[178:181], v6 offset:9216
	s_waitcnt lgkmcnt(3)
	v_mfma_f32_16x16x32_bf16 v[56:59], v[158:161], v[218:221], v[56:59]
	v_mfma_f32_16x16x32_bf16 v[60:63], v[162:165], v[218:221], v[60:63]
	v_mfma_f32_16x16x32_bf16 v[64:67], v[166:169], v[218:221], v[64:67]
	v_mfma_f32_16x16x32_bf16 v[170:173], v[214:217], v[218:221], v[170:173]
	ds_read_b128 v[218:221], v6 offset:11264
	s_waitcnt lgkmcnt(3)
	v_mfma_f32_16x16x32_bf16 v[72:75], v[158:161], v[222:225], v[72:75]
	v_mfma_f32_16x16x32_bf16 v[76:79], v[162:165], v[222:225], v[76:79]
	v_mfma_f32_16x16x32_bf16 v[80:83], v[166:169], v[222:225], v[80:83]
	v_mfma_f32_16x16x32_bf16 v[32:35], v[214:217], v[222:225], v[32:35]
	ds_read_b128 v[222:225], v6 offset:13312
	s_waitcnt lgkmcnt(3)
	v_mfma_f32_16x16x32_bf16 v[88:91], v[158:161], v[226:229], v[88:91]
	v_mfma_f32_16x16x32_bf16 v[92:95], v[162:165], v[226:229], v[92:95]
	v_mfma_f32_16x16x32_bf16 v[96:99], v[166:169], v[226:229], v[96:99]
	v_mfma_f32_16x16x32_bf16 v[36:39], v[214:217], v[226:229], v[36:39]
	ds_read_b128 v[226:229], v6 offset:15360
	s_waitcnt lgkmcnt(3)
	v_mfma_f32_16x16x32_bf16 v[104:107], v[158:161], v[178:181], v[104:107]
	v_mfma_f32_16x16x32_bf16 v[108:111], v[162:165], v[178:181], v[108:111]
	v_mfma_f32_16x16x32_bf16 v[112:115], v[166:169], v[178:181], v[112:115]
	v_mfma_f32_16x16x32_bf16 v[52:55], v[214:217], v[178:181], v[52:55]
	s_waitcnt lgkmcnt(2)
	v_mfma_f32_16x16x32_bf16 v[116:119], v[158:161], v[218:221], v[116:119]
	v_mfma_f32_16x16x32_bf16 v[120:123], v[162:165], v[218:221], v[120:123]
	v_mfma_f32_16x16x32_bf16 v[124:127], v[166:169], v[218:221], v[124:127]
	v_mfma_f32_16x16x32_bf16 v[68:71], v[214:217], v[218:221], v[68:71]
	s_waitcnt lgkmcnt(1)
	v_mfma_f32_16x16x32_bf16 v[132:135], v[162:165], v[222:225], v[132:135]
	v_mfma_f32_16x16x32_bf16 v[84:87], v[214:217], v[222:225], v[84:87]
	s_waitcnt lgkmcnt(0)
	v_mfma_f32_16x16x32_bf16 v[100:103], v[158:161], v[226:229], v[100:103]
	v_mfma_f32_16x16x32_bf16 v[150:153], v[166:169], v[226:229], v[150:153]
	v_mfma_f32_16x16x32_bf16 v[154:157], v[214:217], v[226:229], v[154:157]
	v_mfma_f32_16x16x32_bf16 v[128:131], v[158:161], v[222:225], v[128:131]
	v_mfma_f32_16x16x32_bf16 v[136:139], v[166:169], v[222:225], v[136:139]
	v_mfma_f32_16x16x32_bf16 v[140:143], v[162:165], v[226:229], v[140:143]
	s_waitcnt vmcnt(0)
	s_barrier
	v_lshl_add_u64 v[6:7], s[16:17], 0, v[0:1]
	s_mov_b32 s0, m0
	s_mov_b32 m0, s27
	s_nop 0
	global_load_lds_dwordx4 v[6:7], off
	s_mov_b32 m0, s0
	v_lshl_add_u64 v[0:1], s[18:19], 0, v[0:1]
	s_mov_b32 s0, m0
	s_mov_b32 m0, s28
	s_nop 0
	global_load_lds_dwordx4 v[0:1], off
	s_mov_b32 m0, s0
	v_lshl_add_u64 v[0:1], s[16:17], 0, v[2:3]
	s_mov_b32 s0, m0
	s_mov_b32 m0, s29
	s_nop 0
	global_load_lds_dwordx4 v[0:1], off
	s_mov_b32 m0, s0
	v_lshl_add_u64 v[0:1], s[18:19], 0, v[2:3]
	s_mov_b32 s0, m0
	s_mov_b32 m0, s30
	s_nop 0
	global_load_lds_dwordx4 v[0:1], off
	s_mov_b32 m0, s0
	v_lshl_add_u64 v[0:1], s[16:17], 0, v[4:5]
	s_mov_b32 s0, m0
	s_mov_b32 m0, s31
	s_nop 0
	global_load_lds_dwordx4 v[0:1], off
	s_mov_b32 m0, s0
	v_lshl_add_u64 v[0:1], s[18:19], 0, v[4:5]
	s_mov_b32 s0, m0
	s_mov_b32 m0, s34
	s_nop 0
	global_load_lds_dwordx4 v[0:1], off
	s_mov_b32 m0, s0
	v_lshl_add_u64 v[0:1], s[16:17], 0, v[146:147]
	s_mov_b32 s0, m0
	s_mov_b32 m0, s35
	s_nop 0
	global_load_lds_dwordx4 v[0:1], off
	s_mov_b32 m0, s0
	v_lshl_add_u64 v[0:1], s[18:19], 0, v[146:147]
	s_mov_b32 s0, m0
	s_mov_b32 m0, s36
	s_nop 0
	global_load_lds_dwordx4 v[0:1], off
	s_mov_b32 m0, s0
	ds_read_b128 v[0:3], v8
	ds_read_b128 v[4:7], v9
	ds_read_b128 v[158:161], v11
	ds_read_b128 v[8:11], v10
	ds_read_b128 v[162:165], v12
	ds_read_b128 v[166:169], v13
	ds_read_b128 v[178:181], v14
	ds_read_b128 v[12:15], v15
	s_waitcnt lgkmcnt(3)
	v_mfma_f32_16x16x32_bf16 v[40:43], v[0:3], v[162:165], v[40:43]
	v_mfma_f32_16x16x32_bf16 v[44:47], v[4:7], v[162:165], v[44:47]
	v_mfma_f32_16x16x32_bf16 v[48:51], v[158:161], v[162:165], v[48:51]
	v_mfma_f32_16x16x32_bf16 v[162:165], v[8:11], v[162:165], v[174:177]
	s_nop 2
	ds_read_b128 v[174:177], v16
	s_waitcnt lgkmcnt(3)
	v_mfma_f32_16x16x32_bf16 v[56:59], v[0:3], v[166:169], v[56:59]
	v_mfma_f32_16x16x32_bf16 v[60:63], v[4:7], v[166:169], v[60:63]
	v_mfma_f32_16x16x32_bf16 v[64:67], v[158:161], v[166:169], v[64:67]
	v_mfma_f32_16x16x32_bf16 v[166:169], v[8:11], v[166:169], v[170:173]
	s_nop 2
	ds_read_b128 v[170:173], v17
	s_waitcnt lgkmcnt(3)
	v_mfma_f32_16x16x32_bf16 v[72:75], v[0:3], v[178:181], v[72:75]
	v_mfma_f32_16x16x32_bf16 v[76:79], v[4:7], v[178:181], v[76:79]
	v_mfma_f32_16x16x32_bf16 v[80:83], v[158:161], v[178:181], v[80:83]
	v_mfma_f32_16x16x32_bf16 v[32:35], v[8:11], v[178:181], v[32:35]
	ds_read_b128 v[178:181], v18
	s_waitcnt lgkmcnt(3)
	v_mfma_f32_16x16x32_bf16 v[214:217], v[0:3], v[12:15], v[88:91]
	v_mfma_f32_16x16x32_bf16 v[218:221], v[4:7], v[12:15], v[92:95]
	v_mfma_f32_16x16x32_bf16 v[222:225], v[158:161], v[12:15], v[96:99]
	v_mfma_f32_16x16x32_bf16 v[12:15], v[8:11], v[12:15], v[36:39]
	ds_read_b128 v[16:19], v19
	s_waitcnt lgkmcnt(3)
	v_mfma_f32_16x16x32_bf16 v[36:39], v[0:3], v[174:177], v[104:107]
	v_mfma_f32_16x16x32_bf16 v[226:229], v[4:7], v[174:177], v[108:111]
	v_mfma_f32_16x16x32_bf16 v[112:115], v[158:161], v[174:177], v[112:115]
	s_waitcnt lgkmcnt(2)
	v_mfma_f32_16x16x32_bf16 v[116:119], v[0:3], v[170:173], v[116:119]
	v_mfma_f32_16x16x32_bf16 v[120:123], v[4:7], v[170:173], v[120:123]
	v_mfma_f32_16x16x32_bf16 v[124:127], v[158:161], v[170:173], v[124:127]
	s_waitcnt lgkmcnt(1)
	v_mfma_f32_16x16x32_bf16 v[128:131], v[0:3], v[178:181], v[128:131]
	v_mfma_f32_16x16x32_bf16 v[132:135], v[4:7], v[178:181], v[132:135]
	s_waitcnt lgkmcnt(0)
	v_mfma_f32_16x16x32_bf16 v[0:3], v[0:3], v[16:19], v[100:103]
	v_mfma_f32_16x16x32_bf16 v[4:7], v[4:7], v[16:19], v[140:143]
	v_mfma_f32_16x16x32_bf16 v[140:143], v[158:161], v[16:19], v[150:153]
	v_mfma_f32_16x16x32_bf16 v[150:153], v[8:11], v[16:19], v[154:157]
	v_mfma_f32_16x16x32_bf16 v[174:177], v[8:11], v[174:177], v[52:55]
	v_mfma_f32_16x16x32_bf16 v[170:173], v[8:11], v[170:173], v[68:71]
	v_mfma_f32_16x16x32_bf16 v[136:139], v[158:161], v[178:181], v[136:139]
	v_mfma_f32_16x16x32_bf16 v[178:181], v[8:11], v[178:181], v[84:87]
	ds_read_b128 v[8:11], v20
	ds_read_b128 v[154:157], v21
	ds_read_b128 v[158:161], v23
	ds_read_b128 v[230:233], v22
	ds_read_b128 v[16:19], v24
	ds_read_b128 v[20:23], v25
	ds_read_b128 v[52:55], v26
	ds_read_b128 v[24:27], v27
	s_waitcnt lgkmcnt(3)
	v_mfma_f32_16x16x32_bf16 v[234:237], v[8:11], v[16:19], v[40:43]
	v_mfma_f32_16x16x32_bf16 v[238:241], v[154:157], v[16:19], v[44:47]
	v_mfma_f32_16x16x32_bf16 v[242:245], v[158:161], v[16:19], v[48:51]
	v_mfma_f32_16x16x32_bf16 v[162:165], v[230:233], v[16:19], v[162:165]
	ds_read_b128 v[16:19], v28
	s_waitcnt lgkmcnt(3)
	v_mfma_f32_16x16x32_bf16 v[108:111], v[8:11], v[20:23], v[56:59]
	v_mfma_f32_16x16x32_bf16 v[104:107], v[154:157], v[20:23], v[60:63]
	v_mfma_f32_16x16x32_bf16 v[100:103], v[158:161], v[20:23], v[64:67]
	v_mfma_f32_16x16x32_bf16 v[96:99], v[230:233], v[20:23], v[166:169]
	ds_read_b128 v[20:23], v29
	s_waitcnt lgkmcnt(3)
	v_mfma_f32_16x16x32_bf16 v[92:95], v[8:11], v[52:55], v[72:75]
	v_mfma_f32_16x16x32_bf16 v[88:91], v[154:157], v[52:55], v[76:79]
	v_mfma_f32_16x16x32_bf16 v[84:87], v[158:161], v[52:55], v[80:83]
	v_mfma_f32_16x16x32_bf16 v[80:83], v[230:233], v[52:55], v[32:35]
	ds_read_b128 v[166:169], v30
	s_waitcnt lgkmcnt(3)
	v_mfma_f32_16x16x32_bf16 v[76:79], v[8:11], v[24:27], v[214:217]
	v_mfma_f32_16x16x32_bf16 v[72:75], v[154:157], v[24:27], v[218:221]
	v_mfma_f32_16x16x32_bf16 v[68:71], v[158:161], v[24:27], v[222:225]
	v_mfma_f32_16x16x32_bf16 v[64:67], v[230:233], v[24:27], v[12:15]
	ds_read_b128 v[214:217], v31
	s_waitcnt lgkmcnt(3)
	v_mfma_f32_16x16x32_bf16 v[60:63], v[8:11], v[16:19], v[36:39]
	v_mfma_f32_16x16x32_bf16 v[56:59], v[154:157], v[16:19], v[226:229]
	v_mfma_f32_16x16x32_bf16 v[52:55], v[158:161], v[16:19], v[112:115]
	v_mfma_f32_16x16x32_bf16 v[48:51], v[230:233], v[16:19], v[174:177]
	s_waitcnt lgkmcnt(2)
	v_mfma_f32_16x16x32_bf16 v[44:47], v[8:11], v[20:23], v[116:119]
	v_mfma_f32_16x16x32_bf16 v[40:43], v[154:157], v[20:23], v[120:123]
	v_mfma_f32_16x16x32_bf16 v[36:39], v[158:161], v[20:23], v[124:127]
	v_mfma_f32_16x16x32_bf16 v[32:35], v[230:233], v[20:23], v[170:173]
	s_waitcnt lgkmcnt(1)
	v_mfma_f32_16x16x32_bf16 v[28:31], v[8:11], v[166:169], v[128:131]
	v_mfma_f32_16x16x32_bf16 v[24:27], v[154:157], v[166:169], v[132:135]
	v_mfma_f32_16x16x32_bf16 v[20:23], v[158:161], v[166:169], v[136:139]
	v_mfma_f32_16x16x32_bf16 v[16:19], v[230:233], v[166:169], v[178:181]
	s_waitcnt lgkmcnt(0)
	v_mfma_f32_16x16x32_bf16 v[12:15], v[8:11], v[214:217], v[0:3]
	v_mfma_f32_16x16x32_bf16 v[8:11], v[154:157], v[214:217], v[4:7]
	v_mfma_f32_16x16x32_bf16 v[4:7], v[158:161], v[214:217], v[140:143]
	v_mfma_f32_16x16x32_bf16 v[0:3], v[230:233], v[214:217], v[150:153]
	v_mov_b32_e32 v145, v184
	s_waitcnt vmcnt(0)
	s_barrier
	s_lshl_b32 s16, s13, 8
	s_lshl_b32 s14, s12, 8
	v_and_b32_e32 v151, 15, v145
	v_ashrrev_i32_e32 v112, 1, v145
	v_and_b32_e32 v153, 0xffffff80, v112
	v_or_b32_e32 v112, s16, v151
	v_add_u32_e32 v112, v112, v153
	v_ashrrev_i32_e32 v113, 31, v112
	v_lshlrev_b64 v[112:113], 13, v[112:113]
	v_bfe_u32 v150, v145, 6, 2
	v_lshl_add_u64 v[112:113], s[4:5], 0, v[112:113]
	s_ashr_i32 s15, s14, 31
	v_bfe_u32 v152, v145, 4, 2
	v_lshl_add_u64 v[112:113], s[14:15], 2, v[112:113]
	v_lshlrev_b32_e32 v146, 8, v150
	v_lshl_add_u64 v[112:113], v[112:113], 0, v[146:147]
	v_lshlrev_b32_e32 v146, 4, v152
	v_lshl_add_u64 v[154:155], v[112:113], 0, v[146:147]
	global_load_dwordx4 v[120:123], v[154:155], off offset:192
	global_load_dwordx4 v[128:131], v[154:155], off offset:128
	global_load_dwordx4 v[136:139], v[154:155], off offset:64
	global_load_dwordx4 v[140:143], v[154:155], off
	v_add_co_u32_e32 v112, vcc, s66, v154
	v_lshlrev_b32_e32 v158, 2, v152
	s_nop 0
	v_addc_co_u32_e32 v113, vcc, 0, v155, vcc
	global_load_dwordx4 v[132:135], v[112:113], off
	global_load_dwordx4 v[124:127], v[112:113], off offset:64
	global_load_dwordx4 v[116:119], v[112:113], off offset:128
	v_cmp_lt_i32_e32 vcc, v188, v186
	global_load_dwordx4 v[112:115], v[112:113], off offset:192
	v_cmp_eq_u32_e64 s[0:1], 0, v152
	v_cndmask_b32_e32 v146, v185, v188, vcc
	v_cmp_lt_i32_e32 vcc, v187, v186
	v_lshlrev_b32_e32 v149, 2, v146
	v_lshlrev_b32_e32 v157, 6, v150
	v_cndmask_b32_e32 v156, v185, v187, vcc
	v_lshlrev_b32_e32 v146, 2, v156
	v_or_b32_e32 v156, v153, v151
	v_add_u32_e32 v152, s16, v156
	v_ashrrev_i32_e32 v153, 31, v152
	v_lshl_or_b32 v182, v150, 10, v204
	v_or3_b32 v150, v157, s14, v158
	v_lshlrev_b64 v[158:159], 13, v[152:153]
	v_ashrrev_i32_e32 v151, 31, v150
	v_lshlrev_b64 v[160:161], 12, v[152:153]
	v_lshl_add_u64 v[158:159], s[4:5], 0, v[158:159]
	v_lshl_add_u64 v[160:161], s[6:7], 0, v[160:161]
	v_lshl_add_u64 v[166:167], v[150:151], 2, v[158:159]
	v_lshl_add_u64 v[168:169], v[150:151], 1, v[160:161]
	s_waitcnt vmcnt(7)
	v_pk_add_f32 v[158:159], v[162:163], v[120:121]
	s_waitcnt vmcnt(6)
	v_pk_add_f32 v[120:121], v[242:243], v[128:129]
	s_waitcnt vmcnt(5)
	v_pk_add_f32 v[128:129], v[238:239], v[136:137]
	s_waitcnt vmcnt(4)
	v_pk_add_f32 v[136:137], v[234:235], v[140:141]
	v_pk_add_f32 v[160:161], v[164:165], v[122:123]
	v_pk_add_f32 v[122:123], v[244:245], v[130:131]
	v_pk_add_f32 v[130:131], v[240:241], v[138:139]
	v_pk_add_f32 v[138:139], v[236:237], v[142:143]
	v_pk_mul_f32 v[172:173], v[128:129], v[128:129]
	v_pk_mul_f32 v[178:179], v[136:137], v[136:137]
	v_pk_mul_f32 v[162:163], v[120:121], v[120:121]
	v_pk_mul_f32 v[174:175], v[130:131], v[130:131]
	v_cvt_pk_bf16_f32 v176, v136, v137
	v_pk_mul_f32 v[180:181], v[138:139], v[138:139]
	global_store_dwordx4 v[166:167], v[136:139], off
	v_add_f32_e32 v153, v172, v173
	v_add_f32_e32 v157, v178, v179
	v_pk_mul_f32 v[136:137], v[158:159], v[158:159]
	v_pk_mul_f32 v[164:165], v[122:123], v[122:123]
	v_cvt_pk_bf16_f32 v177, v138, v139
	v_pk_mul_f32 v[138:139], v[160:161], v[160:161]
	v_add_f32_e32 v162, v162, v163
	v_add_f32_e32 v136, v136, v137
	v_add_f32_e32 v137, v174, v153
	v_add_f32_e32 v153, v180, v157
	v_add_f32_e32 v157, v164, v162
	v_add_f32_e32 v136, v138, v136
	v_add_f32_e32 v137, v175, v137
	v_add_f32_e32 v138, v181, v153
	v_add_f32_e32 v153, v165, v157
	v_add_f32_e32 v137, v138, v137
	v_add_f32_e32 v137, v137, v153
	v_add_f32_e32 v136, v139, v136
	v_add_f32_e32 v136, v137, v136
	ds_bpermute_b32 v137, v149, v136
	v_cvt_pk_bf16_f32 v170, v128, v129
	v_cvt_pk_bf16_f32 v171, v130, v131
	v_cvt_pk_bf16_f32 v142, v120, v121
	global_store_dwordx2 v[168:169], v[176:177], off
	global_store_dwordx4 v[166:167], v[128:131], off offset:64
	global_store_dwordx2 v[168:169], v[170:171], off offset:32
	global_store_dwordx4 v[166:167], v[120:123], off offset:128
	v_cvt_pk_bf16_f32 v140, v158, v159
	v_cvt_pk_bf16_f32 v141, v160, v161
	s_waitcnt lgkmcnt(0)
	v_add_f32_e32 v120, v136, v137
	ds_bpermute_b32 v121, v146, v120
	v_cvt_pk_bf16_f32 v143, v122, v123
	v_lshl_add_u32 v153, v156, 2, v182
	global_store_dwordx2 v[168:169], v[142:143], off offset:64
	global_store_dwordx4 v[166:167], v[158:161], off offset:192
	global_store_dwordx2 v[168:169], v[140:141], off offset:96
	s_and_saveexec_b64 s[14:15], s[0:1]
	s_cbranch_execz .LBB0_254
	s_waitcnt lgkmcnt(0)
	v_add_f32_e32 v120, v120, v121
	ds_write_b32 v153, v120

.LBB0_300:
	s_ashr_i32 s31, s30, 31
	s_lshl_b64 s[30:31], s[30:31], 20
	s_add_u32 s30, s38, s30
	s_addc_u32 s31, s39, s31
	s_ashr_i32 s5, s4, 31
	v_lshlrev_b32_e32 v3, 6, v1
	s_lshl_b64 s[4:5], s[4:5], 20
	v_and_b32_e32 v2, 48, v1
	v_and_b32_e32 v4, 0x3c0, v3
	v_lshlrev_b32_e32 v1, 2, v1
	s_add_u32 s34, s14, s4
	v_or_b32_e32 v5, v4, v2
	v_and_b32_e32 v1, 32, v1
	v_lshlrev_b32_e32 v0, 13, v0
	s_mov_b32 s4, 0x18000
	v_and_b32_e32 v135, 0x6000, v0
	v_bitop3_b32 v0, v5, s4, v1 bitop3:0xde
	s_mov_b32 s4, 0x10400
	s_addc_u32 s35, s15, s5
	v_bitop3_b32 v149, v5, s4, v1 bitop3:0xde
	s_lshl_b32 s4, s65, 2
	s_or_b32 s4, s4, s68
	s_lshl_b32 s5, s64, 2
	s_sub_i32 s4, s4, s5
	s_ashr_i32 s5, s4, 31
	s_waitcnt vmcnt(0)
	s_add_i32 s51, s1, 0x10000
	s_add_i32 s52, s1, 0x18000
	s_add_i32 s53, s1, 0x12000
	s_add_i32 s54, s1, 0x1a000
	s_add_i32 s55, s1, 0x14000
	s_add_i32 s58, s1, 0x1c000
	s_add_i32 s62, s1, 0x16000
	s_add_i32 s63, s1, 0x1e000
	s_lshl_b64 s[4:5], s[4:5], 20
	v_and_b32_e32 v136, 0xffffc000, v3
	s_add_u32 s64, s10, s4
	v_mov_b32_e32 v16, 0
	v_bitop3_b32 v134, v4, v1, v2 bitop3:0x36
	v_or_b32_e32 v137, 0x800, v136
	v_or_b32_e32 v138, 0x1000, v136
	v_or_b32_e32 v139, 0x1800, v136
	v_or_b32_e32 v140, 0x2000, v136
	v_or_b32_e32 v141, 0x2800, v136
	v_or_b32_e32 v142, 0x3000, v136
	v_or_b32_e32 v143, 0x3800, v136
	v_bitop3_b32 v145, v5, s33, v1 bitop3:0xde
	s_addc_u32 s65, s11, s5
	s_mov_b64 s[4:5], 0
	s_mov_b32 s68, 1
	v_add_u32_e32 v150, v0, v135
	v_mov_b32_e32 v17, v16
	v_mov_b32_e32 v18, v16
	v_mov_b32_e32 v19, v16
	v_mov_b32_e32 v20, v16
	v_mov_b32_e32 v21, v16
	v_mov_b32_e32 v22, v16
	v_mov_b32_e32 v23, v16
	v_mov_b32_e32 v24, v16
	v_mov_b32_e32 v25, v16
	v_mov_b32_e32 v26, v16
	v_mov_b32_e32 v27, v16
	v_mov_b32_e32 v28, v16
	v_mov_b32_e32 v29, v16
	v_mov_b32_e32 v30, v16
	v_mov_b32_e32 v31, v16
	v_mov_b32_e32 v32, v16
	v_mov_b32_e32 v33, v16
	v_mov_b32_e32 v34, v16
	v_mov_b32_e32 v35, v16
	v_mov_b32_e32 v36, v16
	v_mov_b32_e32 v37, v16
	v_mov_b32_e32 v38, v16
	v_mov_b32_e32 v39, v16
	v_mov_b32_e32 v40, v16
	v_mov_b32_e32 v41, v16
	v_mov_b32_e32 v42, v16
	v_mov_b32_e32 v43, v16
	v_mov_b32_e32 v44, v16
	v_mov_b32_e32 v45, v16
	v_mov_b32_e32 v46, v16
	v_mov_b32_e32 v47, v16
	v_mov_b32_e32 v48, v16
	v_mov_b32_e32 v49, v16
	v_mov_b32_e32 v50, v16
	v_mov_b32_e32 v51, v16
	v_mov_b32_e32 v52, v16
	v_mov_b32_e32 v53, v16
	v_mov_b32_e32 v54, v16
	v_mov_b32_e32 v55, v16
	v_mov_b32_e32 v56, v16
	v_mov_b32_e32 v57, v16
	v_mov_b32_e32 v58, v16
	v_mov_b32_e32 v59, v16
	v_mov_b32_e32 v60, v16
	v_mov_b32_e32 v61, v16
	v_mov_b32_e32 v62, v16
	v_mov_b32_e32 v63, v16
	v_mov_b32_e32 v64, v16
	v_mov_b32_e32 v65, v16
	v_mov_b32_e32 v66, v16
	v_mov_b32_e32 v67, v16
	v_mov_b32_e32 v68, v16
	v_mov_b32_e32 v69, v16
	v_mov_b32_e32 v70, v16
	v_mov_b32_e32 v71, v16
	v_mov_b32_e32 v72, v16
	v_mov_b32_e32 v73, v16
	v_mov_b32_e32 v74, v16
	v_mov_b32_e32 v75, v16
	v_mov_b32_e32 v76, v16
	v_mov_b32_e32 v77, v16
	v_mov_b32_e32 v78, v16
	v_mov_b32_e32 v79, v16
	v_mov_b32_e32 v80, v16
	v_mov_b32_e32 v81, v16
	v_mov_b32_e32 v82, v16
	v_mov_b32_e32 v83, v16
	v_mov_b32_e32 v84, v16
	v_mov_b32_e32 v85, v16
	v_mov_b32_e32 v86, v16
	v_mov_b32_e32 v87, v16
	v_mov_b32_e32 v88, v16
	v_mov_b32_e32 v89, v16
	v_mov_b32_e32 v90, v16
	v_mov_b32_e32 v91, v16
	v_mov_b32_e32 v92, v16
	v_mov_b32_e32 v93, v16
	v_mov_b32_e32 v94, v16
	v_mov_b32_e32 v95, v16
	v_mov_b32_e32 v96, v16
	v_mov_b32_e32 v97, v16
	v_mov_b32_e32 v98, v16
	v_mov_b32_e32 v99, v16
	v_mov_b32_e32 v100, v16
	v_mov_b32_e32 v101, v16
	v_mov_b32_e32 v102, v16
	v_mov_b32_e32 v103, v16
	v_mov_b32_e32 v104, v16
	v_mov_b32_e32 v105, v16
	v_mov_b32_e32 v106, v16
	v_mov_b32_e32 v107, v16
	v_mov_b32_e32 v108, v16
	v_mov_b32_e32 v109, v16
	v_mov_b32_e32 v110, v16
	v_mov_b32_e32 v111, v16
	v_mov_b32_e32 v112, v16
	v_mov_b32_e32 v113, v16
	v_mov_b32_e32 v114, v16
	v_mov_b32_e32 v115, v16
	v_mov_b32_e32 v116, v16
	v_mov_b32_e32 v117, v16
	v_mov_b32_e32 v118, v16
	v_mov_b32_e32 v119, v16
	v_mov_b32_e32 v120, v16
	v_mov_b32_e32 v121, v16
	v_mov_b32_e32 v122, v16
	v_mov_b32_e32 v123, v16
	v_mov_b32_e32 v124, v16
	v_mov_b32_e32 v125, v16
	v_mov_b32_e32 v126, v16
	v_mov_b32_e32 v127, v16
	v_mov_b32_e32 v12, v16
	v_mov_b32_e32 v13, v16
	v_mov_b32_e32 v14, v16
	v_mov_b32_e32 v15, v16
	v_mov_b32_e32 v8, v16
	v_mov_b32_e32 v9, v16
	v_mov_b32_e32 v10, v16
	v_mov_b32_e32 v11, v16
	v_mov_b32_e32 v4, v16
	v_mov_b32_e32 v5, v16
	v_mov_b32_e32 v6, v16
	v_mov_b32_e32 v7, v16
	v_mov_b32_e32 v0, v16
	v_mov_b32_e32 v1, v16
	v_mov_b32_e32 v2, v16
	v_mov_b32_e32 v3, v16
	s_waitcnt lgkmcnt(0)
	s_barrier
	s_add_u32 s69, s64, s4
	s_addc_u32 s74, s65, s5
	s_add_u32 s70, s69, 0x1b900080
	s_addc_u32 s71, s74, 0
	s_add_u32 s75, s2, s4
	s_addc_u32 s76, s3, s5
	s_add_u32 s72, s75, 0x80
	s_addc_u32 s73, s76, 0
	v_add_u32_e32 v151, v134, v135
	v_add_u32_e32 v189, v134, v136
	ds_read_b128 v[152:155], v151 offset:32768
	ds_read_b128 v[156:159], v189
	ds_read_b128 v[160:163], v151 offset:34816
	ds_read_b128 v[164:167], v189 offset:2048
	ds_read_b128 v[168:171], v151 offset:36864
	ds_read_b128 v[172:175], v151 offset:38912
	ds_read_b128 v[176:179], v189 offset:4096
	ds_read_b128 v[180:183], v189 offset:6144
	s_branch .Lmy_rot_301
.LBB0_301:
	s_add_u32 s69, s64, s4
	s_addc_u32 s74, s65, s5
	s_add_u32 s70, s69, 0x1b900080
	s_addc_u32 s71, s74, 0
	s_add_u32 s75, s2, s4
	s_addc_u32 s76, s3, s5
	s_add_u32 s72, s75, 0x80
	s_addc_u32 s73, s76, 0
	v_add_u32_e32 v151, v134, v135
	v_add_u32_e32 v189, v134, v136
	ds_read_b128 v[152:155], v151 offset:32768
	ds_read_b128 v[156:159], v189
	v_mfma_f32_16x16x32_bf16 v[28:31], v[160:163], v[176:179], v[28:31]
	v_mfma_f32_16x16x32_bf16 v[12:15], v[160:163], v[180:183], v[12:15]
	ds_read_b128 v[160:163], v151 offset:34816
	v_mfma_f32_16x16x32_bf16 v[24:27], v[164:167], v[176:179], v[24:27]
	v_mfma_f32_16x16x32_bf16 v[8:11], v[164:167], v[180:183], v[8:11]
	ds_read_b128 v[164:167], v189 offset:2048
	v_mfma_f32_16x16x32_bf16 v[20:23], v[168:171], v[176:179], v[20:23]
	v_mfma_f32_16x16x32_bf16 v[4:7], v[168:171], v[180:183], v[4:7]
	ds_read_b128 v[168:171], v151 offset:36864
	v_mfma_f32_16x16x32_bf16 v[16:19], v[172:175], v[176:179], v[16:19]
	v_mfma_f32_16x16x32_bf16 v[0:3], v[172:175], v[180:183], v[0:3]
	ds_read_b128 v[172:175], v151 offset:38912
	ds_read_b128 v[176:179], v189 offset:4096
	ds_read_b128 v[180:183], v189 offset:6144
.Lmy_rot_301:
	s_waitcnt lgkmcnt(6)
	v_mfma_f32_16x16x32_bf16 v[124:127], v[152:155], v[156:159], v[124:127]
	s_waitcnt lgkmcnt(5)
	v_mfma_f32_16x16x32_bf16 v[120:123], v[160:163], v[156:159], v[120:123]
	s_waitcnt lgkmcnt(4)
	s_mov_b32 m0, s51
	v_mfma_f32_16x16x32_bf16 v[108:111], v[152:155], v[164:167], v[108:111]
	global_load_lds_dwordx4 v128, s[70:71]
	v_mfma_f32_16x16x32_bf16 v[104:107], v[160:163], v[164:167], v[104:107]
	s_waitcnt lgkmcnt(3)
	v_mfma_f32_16x16x32_bf16 v[116:119], v[168:171], v[156:159], v[116:119]
	v_mfma_f32_16x16x32_bf16 v[100:103], v[168:171], v[164:167], v[100:103]
	s_waitcnt lgkmcnt(2)
	s_mov_b32 m0, s52
	v_mfma_f32_16x16x32_bf16 v[112:115], v[172:175], v[156:159], v[112:115]
	global_load_lds_dwordx4 v128, s[72:73]
	ds_read_b128 v[156:159], v189 offset:8192
	v_mfma_f32_16x16x32_bf16 v[96:99], v[172:175], v[164:167], v[96:99]
	ds_read_b128 v[164:167], v189 offset:10240
	s_waitcnt lgkmcnt(3)
	v_mfma_f32_16x16x32_bf16 v[92:95], v[152:155], v[176:179], v[92:95]
	v_mfma_f32_16x16x32_bf16 v[88:91], v[160:163], v[176:179], v[88:91]
	s_mov_b32 m0, s53
	v_mfma_f32_16x16x32_bf16 v[84:87], v[168:171], v[176:179], v[84:87]
	global_load_lds_dwordx4 v130, s[70:71]
	v_mfma_f32_16x16x32_bf16 v[80:83], v[172:175], v[176:179], v[80:83]
	ds_read_b128 v[176:179], v189 offset:12288
	s_waitcnt lgkmcnt(3)
	v_mfma_f32_16x16x32_bf16 v[76:79], v[152:155], v[180:183], v[76:79]
	v_mfma_f32_16x16x32_bf16 v[72:75], v[160:163], v[180:183], v[72:75]
	s_mov_b32 m0, s54
	v_mfma_f32_16x16x32_bf16 v[68:71], v[168:171], v[180:183], v[68:71]
	global_load_lds_dwordx4 v130, s[72:73]
	v_mfma_f32_16x16x32_bf16 v[64:67], v[172:175], v[180:183], v[64:67]
	ds_read_b128 v[180:183], v189 offset:14336
	s_waitcnt lgkmcnt(3)
	v_mfma_f32_16x16x32_bf16 v[56:59], v[160:163], v[156:159], v[56:59]
	s_waitcnt lgkmcnt(2)
	v_mfma_f32_16x16x32_bf16 v[40:43], v[160:163], v[164:167], v[40:43]
	s_waitcnt lgkmcnt(1)
	s_mov_b32 m0, s55
	v_mfma_f32_16x16x32_bf16 v[24:27], v[160:163], v[176:179], v[24:27]
	global_load_lds_dwordx4 v132, s[70:71]
	s_waitcnt lgkmcnt(0)
	v_mfma_f32_16x16x32_bf16 v[8:11], v[160:163], v[180:183], v[8:11]
	ds_read_b128 v[160:163], v151 offset:33792
	v_mfma_f32_16x16x32_bf16 v[60:63], v[152:155], v[156:159], v[60:63]
	v_mfma_f32_16x16x32_bf16 v[44:47], v[152:155], v[164:167], v[44:47]
	s_mov_b32 m0, s58
	v_mfma_f32_16x16x32_bf16 v[28:31], v[152:155], v[176:179], v[28:31]
	global_load_lds_dwordx4 v132, s[72:73]
	v_mfma_f32_16x16x32_bf16 v[12:15], v[152:155], v[180:183], v[12:15]
	ds_read_b128 v[152:155], v189 offset:1024
	v_mfma_f32_16x16x32_bf16 v[36:39], v[168:171], v[164:167], v[36:39]
	v_mfma_f32_16x16x32_bf16 v[32:35], v[172:175], v[164:167], v[32:35]
	ds_read_b128 v[164:167], v151 offset:35840
	s_mov_b32 m0, s62
	v_mfma_f32_16x16x32_bf16 v[52:55], v[168:171], v[156:159], v[52:55]
	global_load_lds_dwordx4 v146, s[70:71]
	v_mfma_f32_16x16x32_bf16 v[48:51], v[172:175], v[156:159], v[48:51]
	ds_read_b128 v[156:159], v189 offset:3072
	v_mfma_f32_16x16x32_bf16 v[20:23], v[168:171], v[176:179], v[20:23]
	v_mfma_f32_16x16x32_bf16 v[16:19], v[172:175], v[176:179], v[16:19]
	ds_read_b128 v[176:179], v189 offset:5120
	s_mov_b32 m0, s63
	v_mfma_f32_16x16x32_bf16 v[4:7], v[168:171], v[180:183], v[4:7]
	global_load_lds_dwordx4 v146, s[72:73]
	ds_read_b128 v[168:171], v151 offset:37888
	v_mfma_f32_16x16x32_bf16 v[0:3], v[172:175], v[180:183], v[0:3]
	ds_read_b128 v[172:175], v151 offset:39936
	ds_read_b128 v[180:183], v189 offset:7168
	s_waitcnt lgkmcnt(6)
	v_mfma_f32_16x16x32_bf16 v[124:127], v[160:163], v[152:155], v[124:127]
	s_waitcnt lgkmcnt(5)
	v_mfma_f32_16x16x32_bf16 v[120:123], v[164:167], v[152:155], v[120:123]
	s_waitcnt lgkmcnt(4)
	v_mfma_f32_16x16x32_bf16 v[108:111], v[160:163], v[156:159], v[108:111]
	v_mfma_f32_16x16x32_bf16 v[104:107], v[164:167], v[156:159], v[104:107]
	s_waitcnt lgkmcnt(3)
	v_mfma_f32_16x16x32_bf16 v[92:95], v[160:163], v[176:179], v[92:95]
	v_mfma_f32_16x16x32_bf16 v[88:91], v[164:167], v[176:179], v[88:91]
	s_waitcnt lgkmcnt(2)
	v_mfma_f32_16x16x32_bf16 v[116:119], v[168:171], v[152:155], v[116:119]
	s_waitcnt lgkmcnt(1)
	v_mfma_f32_16x16x32_bf16 v[112:115], v[172:175], v[152:155], v[112:115]
	ds_read_b128 v[152:155], v189 offset:9216
	v_mfma_f32_16x16x32_bf16 v[100:103], v[168:171], v[156:159], v[100:103]
	v_mfma_f32_16x16x32_bf16 v[96:99], v[172:175], v[156:159], v[96:99]
	ds_read_b128 v[156:159], v189 offset:11264
	v_mfma_f32_16x16x32_bf16 v[84:87], v[168:171], v[176:179], v[84:87]
	v_mfma_f32_16x16x32_bf16 v[80:83], v[172:175], v[176:179], v[80:83]
	ds_read_b128 v[176:179], v189 offset:13312
	s_waitcnt lgkmcnt(3)
	v_mfma_f32_16x16x32_bf16 v[76:79], v[160:163], v[180:183], v[76:79]
	v_mfma_f32_16x16x32_bf16 v[72:75], v[164:167], v[180:183], v[72:75]
	v_mfma_f32_16x16x32_bf16 v[68:71], v[168:171], v[180:183], v[68:71]
	v_mfma_f32_16x16x32_bf16 v[64:67], v[172:175], v[180:183], v[64:67]
	ds_read_b128 v[180:183], v189 offset:15360
	s_waitcnt lgkmcnt(3)
	v_mfma_f32_16x16x32_bf16 v[60:63], v[160:163], v[152:155], v[60:63]
	v_mfma_f32_16x16x32_bf16 v[56:59], v[164:167], v[152:155], v[56:59]
	v_mfma_f32_16x16x32_bf16 v[52:55], v[168:171], v[152:155], v[52:55]
	v_mfma_f32_16x16x32_bf16 v[48:51], v[172:175], v[152:155], v[48:51]
	s_waitcnt lgkmcnt(2)
	v_mfma_f32_16x16x32_bf16 v[44:47], v[160:163], v[156:159], v[44:47]
	v_mfma_f32_16x16x32_bf16 v[40:43], v[164:167], v[156:159], v[40:43]
	v_mfma_f32_16x16x32_bf16 v[36:39], v[168:171], v[156:159], v[36:39]
	v_mfma_f32_16x16x32_bf16 v[32:35], v[172:175], v[156:159], v[32:35]
	s_add_u32 s69, s69, 0x1b900100
	s_addc_u32 s70, s74, 0
	s_add_u32 s72, s75, 0x100
	s_addc_u32 s73, s76, 0
	s_cmp_lt_u32 s68, 31
	s_cselect_b32 s71, s70, s31
	s_cselect_b32 s70, s69, s30
	s_waitcnt vmcnt(0)
	s_waitcnt lgkmcnt(0)
	s_barrier
	s_cselect_b32 s73, s73, s35
	s_cselect_b32 s72, s72, s34
	ds_read_b128 v[152:155], v150
	v_add_u32_e32 v151, v145, v136
	ds_read_b128 v[156:159], v151
	v_mfma_f32_16x16x32_bf16 v[28:31], v[160:163], v[176:179], v[28:31]
	v_mfma_f32_16x16x32_bf16 v[12:15], v[160:163], v[180:183], v[12:15]
	ds_read_b128 v[160:163], v150 offset:2048
	v_mfma_f32_16x16x32_bf16 v[24:27], v[164:167], v[176:179], v[24:27]
	v_mfma_f32_16x16x32_bf16 v[8:11], v[164:167], v[180:183], v[8:11]
	v_add_u32_e32 v151, v145, v137
	ds_read_b128 v[164:167], v151
	v_mfma_f32_16x16x32_bf16 v[20:23], v[168:171], v[176:179], v[20:23]
	v_mfma_f32_16x16x32_bf16 v[4:7], v[168:171], v[180:183], v[4:7]
	ds_read_b128 v[168:171], v150 offset:4096
	v_mfma_f32_16x16x32_bf16 v[16:19], v[172:175], v[176:179], v[16:19]
	v_mfma_f32_16x16x32_bf16 v[0:3], v[172:175], v[180:183], v[0:3]
	ds_read_b128 v[172:175], v150 offset:6144
	v_add_u32_e32 v151, v145, v138
	ds_read_b128 v[176:179], v151
	v_add_u32_e32 v151, v145, v139
	ds_read_b128 v[180:183], v151
	s_waitcnt lgkmcnt(6)
	v_mfma_f32_16x16x32_bf16 v[124:127], v[152:155], v[156:159], v[124:127]
	s_waitcnt lgkmcnt(5)
	v_mfma_f32_16x16x32_bf16 v[120:123], v[160:163], v[156:159], v[120:123]
	s_waitcnt lgkmcnt(4)
	s_mov_b32 m0, s1
	v_mfma_f32_16x16x32_bf16 v[108:111], v[152:155], v[164:167], v[108:111]
	global_load_lds_dwordx4 v128, s[70:71]
	v_mfma_f32_16x16x32_bf16 v[104:107], v[160:163], v[164:167], v[104:107]
	s_waitcnt lgkmcnt(3)
	v_mfma_f32_16x16x32_bf16 v[116:119], v[168:171], v[156:159], v[116:119]
	v_mfma_f32_16x16x32_bf16 v[100:103], v[168:171], v[164:167], v[100:103]
	s_waitcnt lgkmcnt(2)
	s_mov_b32 m0, s44
	v_mfma_f32_16x16x32_bf16 v[112:115], v[172:175], v[156:159], v[112:115]
	global_load_lds_dwordx4 v128, s[72:73]
	v_add_u32_e32 v151, v145, v140
	ds_read_b128 v[156:159], v151
	v_mfma_f32_16x16x32_bf16 v[96:99], v[172:175], v[164:167], v[96:99]
	v_add_u32_e32 v151, v145, v141
	ds_read_b128 v[164:167], v151
	s_waitcnt lgkmcnt(3)
	v_mfma_f32_16x16x32_bf16 v[92:95], v[152:155], v[176:179], v[92:95]
	v_mfma_f32_16x16x32_bf16 v[88:91], v[160:163], v[176:179], v[88:91]
	s_mov_b32 m0, s45
	v_mfma_f32_16x16x32_bf16 v[84:87], v[168:171], v[176:179], v[84:87]
	global_load_lds_dwordx4 v130, s[70:71]
	v_mfma_f32_16x16x32_bf16 v[80:83], v[172:175], v[176:179], v[80:83]
	v_add_u32_e32 v151, v145, v142
	ds_read_b128 v[176:179], v151
	s_waitcnt lgkmcnt(3)
	v_mfma_f32_16x16x32_bf16 v[76:79], v[152:155], v[180:183], v[76:79]
	v_mfma_f32_16x16x32_bf16 v[72:75], v[160:163], v[180:183], v[72:75]
	s_mov_b32 m0, s46
	v_mfma_f32_16x16x32_bf16 v[68:71], v[168:171], v[180:183], v[68:71]
	global_load_lds_dwordx4 v130, s[72:73]
	v_mfma_f32_16x16x32_bf16 v[64:67], v[172:175], v[180:183], v[64:67]
	v_add_u32_e32 v151, v145, v143
	ds_read_b128 v[180:183], v151
	s_waitcnt lgkmcnt(3)
	v_mfma_f32_16x16x32_bf16 v[56:59], v[160:163], v[156:159], v[56:59]
	s_waitcnt lgkmcnt(2)
	v_mfma_f32_16x16x32_bf16 v[40:43], v[160:163], v[164:167], v[40:43]
	s_waitcnt lgkmcnt(1)
	s_mov_b32 m0, s47
	v_mfma_f32_16x16x32_bf16 v[24:27], v[160:163], v[176:179], v[24:27]
	global_load_lds_dwordx4 v132, s[70:71]
	s_waitcnt lgkmcnt(0)
	v_mfma_f32_16x16x32_bf16 v[8:11], v[160:163], v[180:183], v[8:11]
	ds_read_b128 v[160:163], v150 offset:1024
	v_mfma_f32_16x16x32_bf16 v[60:63], v[152:155], v[156:159], v[60:63]
	v_mfma_f32_16x16x32_bf16 v[44:47], v[152:155], v[164:167], v[44:47]
	s_mov_b32 m0, s48
	v_mfma_f32_16x16x32_bf16 v[28:31], v[152:155], v[176:179], v[28:31]
	global_load_lds_dwordx4 v132, s[72:73]
	v_mfma_f32_16x16x32_bf16 v[12:15], v[152:155], v[180:183], v[12:15]
	v_add_u32_e32 v151, v149, v136
	ds_read_b128 v[152:155], v151
	v_mfma_f32_16x16x32_bf16 v[36:39], v[168:171], v[164:167], v[36:39]
	v_mfma_f32_16x16x32_bf16 v[32:35], v[172:175], v[164:167], v[32:35]
	ds_read_b128 v[164:167], v150 offset:3072
	s_mov_b32 m0, s49
	v_mfma_f32_16x16x32_bf16 v[52:55], v[168:171], v[156:159], v[52:55]
	global_load_lds_dwordx4 v146, s[70:71]
	v_mfma_f32_16x16x32_bf16 v[48:51], v[172:175], v[156:159], v[48:51]
	v_add_u32_e32 v151, v149, v137
	ds_read_b128 v[156:159], v151
	v_mfma_f32_16x16x32_bf16 v[20:23], v[168:171], v[176:179], v[20:23]
	v_mfma_f32_16x16x32_bf16 v[16:19], v[172:175], v[176:179], v[16:19]
	v_add_u32_e32 v151, v149, v138
	ds_read_b128 v[176:179], v151
	s_mov_b32 m0, s50
	v_mfma_f32_16x16x32_bf16 v[4:7], v[168:171], v[180:183], v[4:7]
	global_load_lds_dwordx4 v146, s[72:73]
	ds_read_b128 v[168:171], v150 offset:5120
	v_mfma_f32_16x16x32_bf16 v[0:3], v[172:175], v[180:183], v[0:3]
	ds_read_b128 v[172:175], v150 offset:7168
	v_add_u32_e32 v151, v149, v139
	ds_read_b128 v[180:183], v151
	s_waitcnt lgkmcnt(6)
	v_mfma_f32_16x16x32_bf16 v[124:127], v[160:163], v[152:155], v[124:127]
	s_waitcnt lgkmcnt(5)
	v_mfma_f32_16x16x32_bf16 v[120:123], v[164:167], v[152:155], v[120:123]
	s_waitcnt lgkmcnt(4)
	v_mfma_f32_16x16x32_bf16 v[108:111], v[160:163], v[156:159], v[108:111]
	v_mfma_f32_16x16x32_bf16 v[104:107], v[164:167], v[156:159], v[104:107]
	s_waitcnt lgkmcnt(3)
	v_mfma_f32_16x16x32_bf16 v[92:95], v[160:163], v[176:179], v[92:95]
	v_mfma_f32_16x16x32_bf16 v[88:91], v[164:167], v[176:179], v[88:91]
	s_waitcnt lgkmcnt(2)
	v_mfma_f32_16x16x32_bf16 v[116:119], v[168:171], v[152:155], v[116:119]
	s_waitcnt lgkmcnt(1)
	v_mfma_f32_16x16x32_bf16 v[112:115], v[172:175], v[152:155], v[112:115]
	v_add_u32_e32 v151, v149, v140
	ds_read_b128 v[152:155], v151
	v_mfma_f32_16x16x32_bf16 v[100:103], v[168:171], v[156:159], v[100:103]
	v_mfma_f32_16x16x32_bf16 v[96:99], v[172:175], v[156:159], v[96:99]
	v_add_u32_e32 v151, v149, v141
	ds_read_b128 v[156:159], v151
	v_mfma_f32_16x16x32_bf16 v[84:87], v[168:171], v[176:179], v[84:87]
	v_mfma_f32_16x16x32_bf16 v[80:83], v[172:175], v[176:179], v[80:83]
	v_add_u32_e32 v151, v149, v142
	ds_read_b128 v[176:179], v151
	s_waitcnt lgkmcnt(3)
	v_mfma_f32_16x16x32_bf16 v[76:79], v[160:163], v[180:183], v[76:79]
	v_mfma_f32_16x16x32_bf16 v[72:75], v[164:167], v[180:183], v[72:75]
	v_mfma_f32_16x16x32_bf16 v[68:71], v[168:171], v[180:183], v[68:71]
	v_mfma_f32_16x16x32_bf16 v[64:67], v[172:175], v[180:183], v[64:67]
	v_add_u32_e32 v151, v149, v143
	ds_read_b128 v[180:183], v151
	s_waitcnt lgkmcnt(3)
	v_mfma_f32_16x16x32_bf16 v[60:63], v[160:163], v[152:155], v[60:63]
	v_mfma_f32_16x16x32_bf16 v[56:59], v[164:167], v[152:155], v[56:59]
	v_mfma_f32_16x16x32_bf16 v[52:55], v[168:171], v[152:155], v[52:55]
	v_mfma_f32_16x16x32_bf16 v[48:51], v[172:175], v[152:155], v[48:51]
	s_waitcnt lgkmcnt(2)
	v_mfma_f32_16x16x32_bf16 v[44:47], v[160:163], v[156:159], v[44:47]
	v_mfma_f32_16x16x32_bf16 v[40:43], v[164:167], v[156:159], v[40:43]
	v_mfma_f32_16x16x32_bf16 v[36:39], v[168:171], v[156:159], v[36:39]
	v_mfma_f32_16x16x32_bf16 v[32:35], v[172:175], v[156:159], v[32:35]
	s_waitcnt vmcnt(0)
	s_add_u32 s4, s4, 0x100
	s_addc_u32 s5, s5, 0
	s_add_i32 s68, s68, 2
	s_cmpk_lg_i32 s4, 0x1000
	s_waitcnt lgkmcnt(0)
	s_barrier
	s_cbranch_scc1 .LBB0_301
	v_mfma_f32_16x16x32_bf16 v[28:31], v[160:163], v[176:179], v[28:31]
	v_mfma_f32_16x16x32_bf16 v[12:15], v[160:163], v[180:183], v[12:15]
	v_mfma_f32_16x16x32_bf16 v[24:27], v[164:167], v[176:179], v[24:27]
	v_mfma_f32_16x16x32_bf16 v[8:11], v[164:167], v[180:183], v[8:11]
	v_mfma_f32_16x16x32_bf16 v[20:23], v[168:171], v[176:179], v[20:23]
	v_mfma_f32_16x16x32_bf16 v[4:7], v[168:171], v[180:183], v[4:7]
	v_mfma_f32_16x16x32_bf16 v[16:19], v[172:175], v[176:179], v[16:19]
	v_mfma_f32_16x16x32_bf16 v[0:3], v[172:175], v[180:183], v[0:3]
	s_nop 15
	s_nop 15
	v_mov_b32_e32 v128, v184
	s_movk_i32 s1, 0xff80
	v_and_b32_e32 v129, 15, v128
	v_ashrrev_i32_e32 v130, 1, v128
	s_lshl_b32 s34, s0, 8
	v_and_or_b32 v163, v130, s1, v129
	s_cmp_lt_i32 s0, 8
	v_lshl_add_u32 v162, v163, 2, v202
	v_and_b32_e32 v164, 0xc0, v128
	s_cselect_b64 s[2:3], -1, 0
	s_cmp_lt_i32 s0, 10
	v_lshrrev_b32_e32 v128, 2, v128
	ds_read_b32 v150, v162
	s_cselect_b64 s[30:31], -1, 0
	s_add_i32 s1, s34, 0xfffff800
	v_and_b32_e32 v145, 12, v128
	v_or_b32_e32 v128, s34, v164
	v_ashrrev_i32_e32 v129, 31, v128
	v_or_b32_e32 v138, s1, v164
	v_add_u32_e32 v142, s43, v163
	s_cmp_gt_i32 s0, 9
	v_lshl_add_u64 v[140:141], v[128:129], 1, s[18:19]
	v_ashrrev_i32_e32 v128, 6, v138
	v_and_b32_e32 v165, 0xf8f, v142
	v_ashrrev_i32_e32 v168, 12, v142
	s_movk_i32 s0, 0xf7f
	v_ashrrev_i32_e32 v139, 31, v138
	v_add_u32_e32 v149, 0xffff8400, v128
	s_mov_b64 s[4:5], -1
	v_cmp_lt_u32_e64 s[0:1], s0, v165
	v_lshlrev_b32_e32 v166, 10, v168
	v_lshlrev_b32_e32 v167, 3, v165
	v_lshlrev_b32_e32 v136, 2, v145
	v_readlane_b32 s68, v253, 18
	s_cbranch_scc1 .LBB0_316
	v_lshlrev_b32_e32 v146, 7, v165
	v_lshl_add_u64 v[128:129], s[6:7], 0, v[146:147]
	v_mov_b32_e32 v137, v147
	v_lshl_add_u64 v[130:131], s[12:13], 0, v[146:147]
	v_lshl_add_u64 v[154:155], v[128:129], 0, v[136:137]
	v_lshl_add_u64 v[156:157], v[130:131], 0, v[136:137]
	global_load_dwordx4 v[128:131], v[154:155], off
	global_load_dwordx4 v[158:161], v[156:157], off
	v_ashrrev_i32_e32 v143, 31, v142
	v_lshlrev_b64 v[132:133], 12, v[142:143]
	s_waitcnt lgkmcnt(0)
	v_pk_mul_f32 v[170:171], v[116:117], v[150:151] op_sel_hi:[1,0]
	v_lshl_add_u64 v[152:153], v[140:141], 0, v[132:133]
	v_pk_mul_f32 v[134:135], v[124:125], v[150:151] op_sel_hi:[1,0]
	s_and_b64 vcc, exec, s[2:3]
	s_waitcnt vmcnt(0)
	v_pk_mul_f32 v[132:133], v[170:171], v[158:159]
	s_nop 0
	v_pk_fma_f32 v[132:133], v[134:135], v[128:129], v[132:133] neg_lo:[0,0,1] neg_hi:[0,0,1]
	v_pk_mul_f32 v[134:135], v[134:135], v[158:159]
	v_pk_mul_f32 v[158:159], v[126:127], v[150:151] op_sel_hi:[1,0]
	v_pk_fma_f32 v[128:129], v[170:171], v[128:129], v[134:135]
	v_pk_mul_f32 v[170:171], v[118:119], v[150:151] op_sel_hi:[1,0]
	s_nop 0
	v_pk_mul_f32 v[134:135], v[170:171], v[160:161]
	s_nop 0
	v_pk_fma_f32 v[134:135], v[158:159], v[130:131], v[134:135] neg_lo:[0,0,1] neg_hi:[0,0,1]
	v_pk_mul_f32 v[158:159], v[158:159], v[160:161]
	s_nop 0
	v_pk_fma_f32 v[130:131], v[170:171], v[130:131], v[158:159]
	s_cbranch_vccz .LBB0_305
	s_mov_b32 s4, 0x3e000000
	v_lshlrev_b32_e32 v146, 1, v145
	v_pk_mul_f32 v[160:161], v[132:133], s[4:5] op_sel_hi:[1,0]
	v_pk_mul_f32 v[170:171], v[134:135], s[4:5] op_sel_hi:[1,0]
	v_lshl_add_u64 v[158:159], v[152:153], 0, v[146:147]
	v_cvt_pk_bf16_f32 v160, v160, v161
	v_cvt_pk_bf16_f32 v161, v170, v171
	global_store_dwordx2 v[158:159], v[160:161], off
	v_pk_mul_f32 v[160:161], v[128:129], s[4:5] op_sel_hi:[1,0]
	v_pk_mul_f32 v[170:171], v[130:131], s[4:5] op_sel_hi:[1,0]
	v_cvt_pk_bf16_f32 v160, v160, v161
	v_cvt_pk_bf16_f32 v161, v170, v171
	s_mov_b64 s[4:5], 0
	global_store_dwordx2 v[158:159], v[160:161], off offset:64

.LBB0_565:
	s_mul_i32 s20, s23, 0x300000
	s_mul_hi_i32 s21, s23, 0x300000
	s_add_u32 s20, s26, s20
	s_addc_u32 s21, s27, s21
	s_mul_hi_i32 s23, s22, 0x300000
	s_mul_i32 s22, s22, 0x300000
	s_add_u32 s22, s38, s22
	s_addc_u32 s23, s39, s23
	s_add_u32 s62, s0, 0x80
	v_and_b32_e32 v8, 48, v7
	v_lshlrev_b32_e32 v9, 6, v7
	v_lshlrev_b32_e32 v7, 2, v7
	s_addc_u32 s63, s1, 0
	v_and_b32_e32 v10, 0x3c0, v9
	v_and_b32_e32 v149, 32, v7
	s_add_u32 s64, s14, 0x80
	v_or_b32_e32 v145, v10, v8
	v_bitop3_b32 v12, v10, v149, v8 bitop3:0x36
	s_waitcnt vmcnt(0)
	s_barrier
	v_lshlrev_b32_e32 v8, 13, v6
	s_addc_u32 s65, s15, 0
	s_add_i32 s52, s42, 0x10000
	v_lshl_add_u64 v[6:7], s[62:63], 0, v[0:1]
	s_mov_b32 s53, m0
	s_mov_b32 m0, s52
	s_nop 0
	global_load_lds_dwordx4 v[6:7], off
	s_mov_b32 m0, s53
	s_add_i32 s51, s42, 0x18000
	v_lshl_add_u64 v[6:7], s[64:65], 0, v[0:1]
	s_mov_b32 s53, m0
	s_mov_b32 m0, s51
	s_nop 0
	global_load_lds_dwordx4 v[6:7], off
	s_mov_b32 m0, s53
	v_lshl_add_u64 v[6:7], s[62:63], 0, v[2:3]
	s_add_i32 s53, s42, 0x12000
	s_mov_b32 s54, m0
	s_mov_b32 m0, s53
	s_nop 0
	global_load_lds_dwordx4 v[6:7], off
	s_mov_b32 m0, s54
	v_lshl_add_u64 v[6:7], s[64:65], 0, v[2:3]
	s_add_i32 s54, s42, 0x1a000
	s_mov_b32 s55, m0
	s_mov_b32 m0, s54
	s_nop 0
	global_load_lds_dwordx4 v[6:7], off
	s_mov_b32 m0, s55
	v_lshl_add_u64 v[6:7], s[62:63], 0, v[4:5]
	s_add_i32 s55, s42, 0x14000
	s_mov_b32 s58, m0
	s_mov_b32 m0, s55
	s_nop 0
	global_load_lds_dwordx4 v[6:7], off
	s_mov_b32 m0, s58
	v_lshl_add_u64 v[6:7], s[64:65], 0, v[4:5]
	s_add_i32 s58, s42, 0x1c000
	s_mov_b32 s68, m0
	s_mov_b32 m0, s58
	s_nop 0
	global_load_lds_dwordx4 v[6:7], off
	s_mov_b32 m0, s68
	v_lshl_add_u64 v[6:7], s[62:63], 0, v[146:147]
	s_add_i32 s62, s42, 0x16000
	s_mov_b32 s63, m0
	s_mov_b32 m0, s62
	s_nop 0
	global_load_lds_dwordx4 v[6:7], off
	s_mov_b32 m0, s63
	v_lshl_add_u64 v[6:7], s[64:65], 0, v[146:147]
	s_add_i32 s63, s42, 0x1e000
	s_mov_b32 s64, m0
	s_mov_b32 m0, s63
	s_nop 0
	global_load_lds_dwordx4 v[6:7], off
	s_mov_b32 m0, s64
	v_and_b32_e32 v182, 0xffffc000, v9
	v_or_b32_e32 v183, 0x800, v182
	v_or_b32_e32 v189, 0x1000, v182
	v_or_b32_e32 v199, 0x1800, v182
	v_or_b32_e32 v200, 0x2000, v182
	v_or_b32_e32 v201, 0x2800, v182
	v_or_b32_e32 v203, 0x3000, v182
	v_or_b32_e32 v206, 0x3800, v182
	s_movk_i32 s64, 0x6000
	v_and_or_b32 v7, v8, s64, v12
	ds_read_b128 v[8:11], v7 offset:32768
	v_or_b32_e32 v6, v12, v182
	ds_read_b128 v[12:15], v7 offset:34816
	ds_read_b128 v[16:19], v7 offset:36864
	ds_read_b128 v[24:27], v7 offset:38912
	ds_read_b128 v[20:23], v6
	ds_read_b128 v[28:31], v6 offset:2048
	ds_read_b128 v[32:35], v6 offset:4096
	ds_read_b128 v[36:39], v6 offset:6144
	s_waitcnt lgkmcnt(3)
	v_mfma_f32_16x16x32_bf16 v[40:43], v[8:11], v[20:23], 0
	v_mfma_f32_16x16x32_bf16 v[44:47], v[12:15], v[20:23], 0
	v_mfma_f32_16x16x32_bf16 v[48:51], v[16:19], v[20:23], 0
	v_mfma_f32_16x16x32_bf16 v[20:23], v[24:27], v[20:23], 0
	ds_read_b128 v[52:55], v6 offset:8192
	s_waitcnt lgkmcnt(3)
	v_mfma_f32_16x16x32_bf16 v[56:59], v[8:11], v[28:31], 0
	v_mfma_f32_16x16x32_bf16 v[60:63], v[12:15], v[28:31], 0
	v_mfma_f32_16x16x32_bf16 v[64:67], v[16:19], v[28:31], 0
	v_mfma_f32_16x16x32_bf16 v[28:31], v[24:27], v[28:31], 0
	ds_read_b128 v[68:71], v6 offset:10240
	s_waitcnt lgkmcnt(3)
	v_mfma_f32_16x16x32_bf16 v[72:75], v[8:11], v[32:35], 0
	v_mfma_f32_16x16x32_bf16 v[76:79], v[12:15], v[32:35], 0
	v_mfma_f32_16x16x32_bf16 v[80:83], v[16:19], v[32:35], 0
	v_mfma_f32_16x16x32_bf16 v[32:35], v[24:27], v[32:35], 0
	ds_read_b128 v[84:87], v6 offset:12288
	s_waitcnt lgkmcnt(3)
	v_mfma_f32_16x16x32_bf16 v[88:91], v[8:11], v[36:39], 0
	v_mfma_f32_16x16x32_bf16 v[92:95], v[12:15], v[36:39], 0
	v_mfma_f32_16x16x32_bf16 v[96:99], v[16:19], v[36:39], 0
	v_mfma_f32_16x16x32_bf16 v[36:39], v[24:27], v[36:39], 0
	ds_read_b128 v[100:103], v6 offset:14336
	s_waitcnt lgkmcnt(3)
	v_mfma_f32_16x16x32_bf16 v[104:107], v[8:11], v[52:55], 0
	v_mfma_f32_16x16x32_bf16 v[108:111], v[12:15], v[52:55], 0
	v_mfma_f32_16x16x32_bf16 v[112:115], v[16:19], v[52:55], 0
	v_mfma_f32_16x16x32_bf16 v[52:55], v[24:27], v[52:55], 0
	s_waitcnt lgkmcnt(2)
	v_mfma_f32_16x16x32_bf16 v[116:119], v[8:11], v[68:71], 0
	v_mfma_f32_16x16x32_bf16 v[120:123], v[12:15], v[68:71], 0
	v_mfma_f32_16x16x32_bf16 v[124:127], v[16:19], v[68:71], 0
	v_mfma_f32_16x16x32_bf16 v[68:71], v[24:27], v[68:71], 0
	s_waitcnt lgkmcnt(1)
	v_mfma_f32_16x16x32_bf16 v[128:131], v[8:11], v[84:87], 0
	v_mfma_f32_16x16x32_bf16 v[132:135], v[12:15], v[84:87], 0
	v_mfma_f32_16x16x32_bf16 v[136:139], v[16:19], v[84:87], 0
	v_mfma_f32_16x16x32_bf16 v[84:87], v[24:27], v[84:87], 0
	s_waitcnt lgkmcnt(0)
	v_mfma_f32_16x16x32_bf16 v[8:11], v[8:11], v[100:103], 0
	v_mfma_f32_16x16x32_bf16 v[12:15], v[12:15], v[100:103], 0
	v_mfma_f32_16x16x32_bf16 v[16:19], v[16:19], v[100:103], 0
	v_mfma_f32_16x16x32_bf16 v[24:27], v[24:27], v[100:103], 0
	ds_read_b128 v[100:103], v7 offset:33792
	ds_read_b128 v[140:143], v7 offset:35840
	ds_read_b128 v[150:153], v7 offset:37888
	ds_read_b128 v[158:161], v7 offset:39936
	ds_read_b128 v[154:157], v6 offset:1024
	ds_read_b128 v[162:165], v6 offset:3072
	ds_read_b128 v[166:169], v6 offset:5120
	ds_read_b128 v[170:173], v6 offset:7168
	s_waitcnt lgkmcnt(3)
	v_mfma_f32_16x16x32_bf16 v[40:43], v[100:103], v[154:157], v[40:43]
	v_mfma_f32_16x16x32_bf16 v[44:47], v[140:143], v[154:157], v[44:47]
	v_mfma_f32_16x16x32_bf16 v[48:51], v[150:153], v[154:157], v[48:51]
	v_mfma_f32_16x16x32_bf16 v[20:23], v[158:161], v[154:157], v[20:23]
	ds_read_b128 v[154:157], v6 offset:9216
	s_waitcnt lgkmcnt(3)
	v_mfma_f32_16x16x32_bf16 v[56:59], v[100:103], v[162:165], v[56:59]
	v_mfma_f32_16x16x32_bf16 v[60:63], v[140:143], v[162:165], v[60:63]
	v_mfma_f32_16x16x32_bf16 v[64:67], v[150:153], v[162:165], v[64:67]
	v_mfma_f32_16x16x32_bf16 v[28:31], v[158:161], v[162:165], v[28:31]
	ds_read_b128 v[162:165], v6 offset:11264
	s_waitcnt lgkmcnt(3)
	v_mfma_f32_16x16x32_bf16 v[72:75], v[100:103], v[166:169], v[72:75]
	v_mfma_f32_16x16x32_bf16 v[76:79], v[140:143], v[166:169], v[76:79]
	v_mfma_f32_16x16x32_bf16 v[80:83], v[150:153], v[166:169], v[80:83]
	v_mfma_f32_16x16x32_bf16 v[32:35], v[158:161], v[166:169], v[32:35]
	ds_read_b128 v[166:169], v6 offset:13312
	s_waitcnt lgkmcnt(3)
	v_mfma_f32_16x16x32_bf16 v[88:91], v[100:103], v[170:173], v[88:91]
	v_mfma_f32_16x16x32_bf16 v[92:95], v[140:143], v[170:173], v[92:95]
	v_mfma_f32_16x16x32_bf16 v[96:99], v[150:153], v[170:173], v[96:99]
	v_mfma_f32_16x16x32_bf16 v[36:39], v[158:161], v[170:173], v[36:39]
	ds_read_b128 v[170:173], v6 offset:15360
	s_waitcnt lgkmcnt(3)
	v_mfma_f32_16x16x32_bf16 v[104:107], v[100:103], v[154:157], v[104:107]
	v_mfma_f32_16x16x32_bf16 v[108:111], v[140:143], v[154:157], v[108:111]
	v_mfma_f32_16x16x32_bf16 v[112:115], v[150:153], v[154:157], v[112:115]
	v_mfma_f32_16x16x32_bf16 v[52:55], v[158:161], v[154:157], v[52:55]
	s_waitcnt lgkmcnt(2)
	v_mfma_f32_16x16x32_bf16 v[116:119], v[100:103], v[162:165], v[116:119]
	v_mfma_f32_16x16x32_bf16 v[120:123], v[140:143], v[162:165], v[120:123]
	v_mfma_f32_16x16x32_bf16 v[124:127], v[150:153], v[162:165], v[124:127]
	v_mfma_f32_16x16x32_bf16 v[68:71], v[158:161], v[162:165], v[68:71]
	s_waitcnt lgkmcnt(1)
	v_mfma_f32_16x16x32_bf16 v[128:131], v[100:103], v[166:169], v[128:131]
	v_mfma_f32_16x16x32_bf16 v[132:135], v[140:143], v[166:169], v[132:135]
	v_mfma_f32_16x16x32_bf16 v[136:139], v[150:153], v[166:169], v[136:139]
	v_mfma_f32_16x16x32_bf16 v[84:87], v[158:161], v[166:169], v[84:87]
	s_waitcnt lgkmcnt(0)
	v_mfma_f32_16x16x32_bf16 v[100:103], v[100:103], v[170:173], v[8:11]
	v_mfma_f32_16x16x32_bf16 v[150:153], v[150:153], v[170:173], v[16:19]
	v_mfma_f32_16x16x32_bf16 v[24:27], v[158:161], v[170:173], v[24:27]
	v_mfma_f32_16x16x32_bf16 v[140:143], v[140:143], v[170:173], v[12:15]
	s_add_u32 s64, s0, 0x100
	s_addc_u32 s65, s1, 0
	s_add_u32 s68, s14, 0x100
	s_waitcnt vmcnt(0)
	s_barrier
	s_addc_u32 s69, s15, 0
	v_lshl_add_u64 v[8:9], s[64:65], 0, v[0:1]
	s_mov_b32 s70, m0
	s_mov_b32 m0, s42
	s_nop 0
	global_load_lds_dwordx4 v[8:9], off
	s_mov_b32 m0, s70
	v_lshl_add_u64 v[8:9], s[68:69], 0, v[0:1]
	s_mov_b32 s70, m0
	s_mov_b32 m0, s43
	s_nop 0
	global_load_lds_dwordx4 v[8:9], off
	s_mov_b32 m0, s70
	v_lshl_add_u64 v[8:9], s[64:65], 0, v[2:3]
	s_mov_b32 s70, m0
	s_mov_b32 m0, s44
	s_nop 0
	global_load_lds_dwordx4 v[8:9], off
	s_mov_b32 m0, s70
	v_lshl_add_u64 v[8:9], s[68:69], 0, v[2:3]
	s_mov_b32 s70, m0
	s_mov_b32 m0, s45
	s_nop 0
	global_load_lds_dwordx4 v[8:9], off
	s_mov_b32 m0, s70
	v_lshl_add_u64 v[8:9], s[64:65], 0, v[4:5]
	s_mov_b32 s70, m0
	s_mov_b32 m0, s46
	s_nop 0
	global_load_lds_dwordx4 v[8:9], off
	s_mov_b32 m0, s70
	v_lshl_add_u64 v[8:9], s[68:69], 0, v[4:5]
	s_mov_b32 s70, m0
	s_mov_b32 m0, s47
	s_nop 0
	global_load_lds_dwordx4 v[8:9], off
	s_mov_b32 m0, s70
	v_lshl_add_u64 v[8:9], s[64:65], 0, v[146:147]
	s_mov_b32 s64, m0
	s_mov_b32 m0, s49
	s_nop 0
	global_load_lds_dwordx4 v[8:9], off
	s_mov_b32 m0, s64
	v_lshl_add_u64 v[8:9], s[68:69], 0, v[146:147]
	s_mov_b32 s64, m0
	s_mov_b32 m0, s50
	s_nop 0
	global_load_lds_dwordx4 v[8:9], off
	s_mov_b32 m0, s64
	v_or_b32_e32 v8, 0x18000, v7
	v_or_b32_e32 v9, 0x18800, v7
	v_or_b32_e32 v11, 0x19000, v7
	v_or_b32_e32 v10, 0x19800, v7
	ds_read_b128 v[154:157], v8
	ds_read_b128 v[158:161], v9
	ds_read_b128 v[162:165], v11
	ds_read_b128 v[166:169], v10
	v_bitop3_b32 v207, v145, s33, v149 bitop3:0xde
	v_add_u32_e32 v12, v207, v182
	ds_read_b128 v[16:19], v12
	v_add_u32_e32 v13, v207, v183
	v_add_u32_e32 v14, v207, v189
	v_add_u32_e32 v15, v207, v199
	ds_read_b128 v[170:173], v13
	ds_read_b128 v[174:177], v14
	ds_read_b128 v[178:181], v15
	s_waitcnt lgkmcnt(3)
	v_mfma_f32_16x16x32_bf16 v[40:43], v[154:157], v[16:19], v[40:43]
	v_mfma_f32_16x16x32_bf16 v[44:47], v[158:161], v[16:19], v[44:47]
	v_mfma_f32_16x16x32_bf16 v[48:51], v[162:165], v[16:19], v[48:51]
	v_mfma_f32_16x16x32_bf16 v[214:217], v[166:169], v[16:19], v[20:23]
	v_add_u32_e32 v16, v207, v200
	v_add_u32_e32 v17, v207, v201
	v_add_u32_e32 v18, v207, v203
	v_add_u32_e32 v19, v207, v206
	ds_read_b128 v[20:23], v16
	s_waitcnt lgkmcnt(3)
	v_mfma_f32_16x16x32_bf16 v[56:59], v[154:157], v[170:173], v[56:59]
	v_mfma_f32_16x16x32_bf16 v[60:63], v[158:161], v[170:173], v[60:63]
	v_mfma_f32_16x16x32_bf16 v[64:67], v[162:165], v[170:173], v[64:67]
	v_mfma_f32_16x16x32_bf16 v[170:173], v[166:169], v[170:173], v[28:31]
	s_nop 2
	ds_read_b128 v[28:31], v17
	s_waitcnt lgkmcnt(3)
	v_mfma_f32_16x16x32_bf16 v[72:75], v[154:157], v[174:177], v[72:75]
	v_mfma_f32_16x16x32_bf16 v[76:79], v[158:161], v[174:177], v[76:79]
	v_mfma_f32_16x16x32_bf16 v[80:83], v[162:165], v[174:177], v[80:83]
	v_mfma_f32_16x16x32_bf16 v[32:35], v[166:169], v[174:177], v[32:35]
	ds_read_b128 v[174:177], v18
	s_waitcnt lgkmcnt(3)
	v_mfma_f32_16x16x32_bf16 v[88:91], v[154:157], v[178:181], v[88:91]
	v_mfma_f32_16x16x32_bf16 v[92:95], v[158:161], v[178:181], v[92:95]
	v_mfma_f32_16x16x32_bf16 v[96:99], v[162:165], v[178:181], v[96:99]
	v_mfma_f32_16x16x32_bf16 v[36:39], v[166:169], v[178:181], v[36:39]
	ds_read_b128 v[178:181], v19
	s_waitcnt lgkmcnt(3)
	v_mfma_f32_16x16x32_bf16 v[104:107], v[154:157], v[20:23], v[104:107]
	v_mfma_f32_16x16x32_bf16 v[108:111], v[158:161], v[20:23], v[108:111]
	v_mfma_f32_16x16x32_bf16 v[112:115], v[162:165], v[20:23], v[112:115]
	v_mfma_f32_16x16x32_bf16 v[52:55], v[166:169], v[20:23], v[52:55]
	s_waitcnt lgkmcnt(2)
	v_mfma_f32_16x16x32_bf16 v[116:119], v[154:157], v[28:31], v[116:119]
	v_mfma_f32_16x16x32_bf16 v[120:123], v[158:161], v[28:31], v[120:123]
	v_mfma_f32_16x16x32_bf16 v[124:127], v[162:165], v[28:31], v[124:127]
	v_mfma_f32_16x16x32_bf16 v[68:71], v[166:169], v[28:31], v[68:71]
	s_waitcnt lgkmcnt(1)
	v_mfma_f32_16x16x32_bf16 v[128:131], v[154:157], v[174:177], v[128:131]
	v_mfma_f32_16x16x32_bf16 v[132:135], v[158:161], v[174:177], v[132:135]
	v_mfma_f32_16x16x32_bf16 v[84:87], v[166:169], v[174:177], v[84:87]
	s_waitcnt lgkmcnt(0)
	v_mfma_f32_16x16x32_bf16 v[100:103], v[154:157], v[178:181], v[100:103]
	v_mfma_f32_16x16x32_bf16 v[150:153], v[162:165], v[178:181], v[150:153]
	v_mfma_f32_16x16x32_bf16 v[154:157], v[166:169], v[178:181], v[24:27]
	v_mfma_f32_16x16x32_bf16 v[136:139], v[162:165], v[174:177], v[136:139]
	v_mfma_f32_16x16x32_bf16 v[140:143], v[158:161], v[178:181], v[140:143]
	v_or_b32_e32 v20, 0x18400, v7
	v_or_b32_e32 v21, 0x18c00, v7
	v_or_b32_e32 v23, 0x19400, v7
	v_or_b32_e32 v22, 0x19c00, v7
	ds_read_b128 v[158:161], v20
	ds_read_b128 v[162:165], v21
	ds_read_b128 v[166:169], v23
	ds_read_b128 v[174:177], v22
	s_mov_b32 s64, 0x10400
	v_bitop3_b32 v145, v145, s64, v149 bitop3:0xde
	v_add_u32_e32 v24, v145, v182
	ds_read_b128 v[28:31], v24
	v_add_u32_e32 v25, v145, v183
	v_add_u32_e32 v26, v145, v189
	v_add_u32_e32 v27, v145, v199
	ds_read_b128 v[178:181], v25
	ds_read_b128 v[218:221], v26
	ds_read_b128 v[222:225], v27
	s_waitcnt lgkmcnt(3)
	v_mfma_f32_16x16x32_bf16 v[40:43], v[158:161], v[28:31], v[40:43]
	v_mfma_f32_16x16x32_bf16 v[44:47], v[162:165], v[28:31], v[44:47]
	v_mfma_f32_16x16x32_bf16 v[48:51], v[166:169], v[28:31], v[48:51]
	v_mfma_f32_16x16x32_bf16 v[214:217], v[174:177], v[28:31], v[214:217]
	v_add_u32_e32 v28, v145, v200
	v_add_u32_e32 v29, v145, v201
	v_add_u32_e32 v30, v145, v203
	v_add_u32_e32 v31, v145, v206
	ds_read_b128 v[226:229], v28
	s_waitcnt lgkmcnt(3)
	v_mfma_f32_16x16x32_bf16 v[56:59], v[158:161], v[178:181], v[56:59]
	v_mfma_f32_16x16x32_bf16 v[60:63], v[162:165], v[178:181], v[60:63]
	v_mfma_f32_16x16x32_bf16 v[64:67], v[166:169], v[178:181], v[64:67]
	v_mfma_f32_16x16x32_bf16 v[170:173], v[174:177], v[178:181], v[170:173]
	ds_read_b128 v[178:181], v29
	s_waitcnt lgkmcnt(3)
	v_mfma_f32_16x16x32_bf16 v[72:75], v[158:161], v[218:221], v[72:75]
	v_mfma_f32_16x16x32_bf16 v[76:79], v[162:165], v[218:221], v[76:79]
	v_mfma_f32_16x16x32_bf16 v[80:83], v[166:169], v[218:221], v[80:83]
	v_mfma_f32_16x16x32_bf16 v[32:35], v[174:177], v[218:221], v[32:35]
	ds_read_b128 v[218:221], v30
	s_waitcnt lgkmcnt(3)
	v_mfma_f32_16x16x32_bf16 v[88:91], v[158:161], v[222:225], v[88:91]
	v_mfma_f32_16x16x32_bf16 v[92:95], v[162:165], v[222:225], v[92:95]
	v_mfma_f32_16x16x32_bf16 v[96:99], v[166:169], v[222:225], v[96:99]
	v_mfma_f32_16x16x32_bf16 v[36:39], v[174:177], v[222:225], v[36:39]
	ds_read_b128 v[222:225], v31
	s_waitcnt lgkmcnt(3)
	v_mfma_f32_16x16x32_bf16 v[104:107], v[158:161], v[226:229], v[104:107]
	v_mfma_f32_16x16x32_bf16 v[108:111], v[162:165], v[226:229], v[108:111]
	v_mfma_f32_16x16x32_bf16 v[112:115], v[166:169], v[226:229], v[112:115]
	v_mfma_f32_16x16x32_bf16 v[52:55], v[174:177], v[226:229], v[52:55]
	s_waitcnt lgkmcnt(2)
	v_mfma_f32_16x16x32_bf16 v[116:119], v[158:161], v[178:181], v[116:119]
	v_mfma_f32_16x16x32_bf16 v[120:123], v[162:165], v[178:181], v[120:123]
	v_mfma_f32_16x16x32_bf16 v[124:127], v[166:169], v[178:181], v[124:127]
	v_mfma_f32_16x16x32_bf16 v[68:71], v[174:177], v[178:181], v[68:71]
	s_waitcnt lgkmcnt(1)
	v_mfma_f32_16x16x32_bf16 v[132:135], v[162:165], v[218:221], v[132:135]
	v_mfma_f32_16x16x32_bf16 v[84:87], v[174:177], v[218:221], v[84:87]
	s_waitcnt lgkmcnt(0)
	v_mfma_f32_16x16x32_bf16 v[100:103], v[158:161], v[222:225], v[100:103]
	v_mfma_f32_16x16x32_bf16 v[150:153], v[166:169], v[222:225], v[150:153]
	v_mfma_f32_16x16x32_bf16 v[154:157], v[174:177], v[222:225], v[154:157]
	v_mfma_f32_16x16x32_bf16 v[128:131], v[158:161], v[218:221], v[128:131]
	v_mfma_f32_16x16x32_bf16 v[136:139], v[166:169], v[218:221], v[136:139]
	v_mfma_f32_16x16x32_bf16 v[140:143], v[162:165], v[222:225], v[140:143]
	s_add_u32 s64, s0, 0x180
	s_addc_u32 s65, s1, 0
	s_add_u32 s68, s14, 0x180
	s_waitcnt vmcnt(0)
	s_barrier
	s_addc_u32 s69, s15, 0
	v_lshl_add_u64 v[158:159], s[64:65], 0, v[0:1]
	s_mov_b32 s70, m0
	s_mov_b32 m0, s52
	s_nop 0
	global_load_lds_dwordx4 v[158:159], off
	s_mov_b32 m0, s70
	v_lshl_add_u64 v[158:159], s[68:69], 0, v[0:1]
	s_mov_b32 s70, m0
	s_mov_b32 m0, s51
	s_nop 0
	global_load_lds_dwordx4 v[158:159], off
	s_mov_b32 m0, s70
	v_lshl_add_u64 v[158:159], s[64:65], 0, v[2:3]
	s_mov_b32 s70, m0
	s_mov_b32 m0, s53
	s_nop 0
	global_load_lds_dwordx4 v[158:159], off
	s_mov_b32 m0, s70
	v_lshl_add_u64 v[158:159], s[68:69], 0, v[2:3]
	s_mov_b32 s70, m0
	s_mov_b32 m0, s54
	s_nop 0
	global_load_lds_dwordx4 v[158:159], off
	s_mov_b32 m0, s70
	v_lshl_add_u64 v[158:159], s[64:65], 0, v[4:5]
	s_mov_b32 s70, m0
	s_mov_b32 m0, s55
	s_nop 0
	global_load_lds_dwordx4 v[158:159], off
	s_mov_b32 m0, s70
	v_lshl_add_u64 v[158:159], s[68:69], 0, v[4:5]
	s_mov_b32 s70, m0
	s_mov_b32 m0, s58
	s_nop 0
	global_load_lds_dwordx4 v[158:159], off
	s_mov_b32 m0, s70
	v_lshl_add_u64 v[158:159], s[64:65], 0, v[146:147]
	s_mov_b32 s64, m0
	s_mov_b32 m0, s62
	s_nop 0
	global_load_lds_dwordx4 v[158:159], off
	s_mov_b32 m0, s64
	v_lshl_add_u64 v[158:159], s[68:69], 0, v[146:147]
	s_mov_b32 s64, m0
	s_mov_b32 m0, s63
	s_nop 0
	global_load_lds_dwordx4 v[158:159], off
	s_mov_b32 m0, s64
	ds_read_b128 v[158:161], v7 offset:32768
	ds_read_b128 v[162:165], v7 offset:34816
	ds_read_b128 v[166:169], v7 offset:36864
	ds_read_b128 v[178:181], v7 offset:38912
	ds_read_b128 v[174:177], v6
	ds_read_b128 v[218:221], v6 offset:2048
	ds_read_b128 v[222:225], v6 offset:4096
	ds_read_b128 v[226:229], v6 offset:6144
	s_waitcnt lgkmcnt(3)
	v_mfma_f32_16x16x32_bf16 v[40:43], v[158:161], v[174:177], v[40:43]
	v_mfma_f32_16x16x32_bf16 v[44:47], v[162:165], v[174:177], v[44:47]
	v_mfma_f32_16x16x32_bf16 v[48:51], v[166:169], v[174:177], v[48:51]
	v_mfma_f32_16x16x32_bf16 v[174:177], v[178:181], v[174:177], v[214:217]
	s_nop 2
	ds_read_b128 v[214:217], v6 offset:8192
	s_waitcnt lgkmcnt(3)
	v_mfma_f32_16x16x32_bf16 v[56:59], v[158:161], v[218:221], v[56:59]
	v_mfma_f32_16x16x32_bf16 v[60:63], v[162:165], v[218:221], v[60:63]
	v_mfma_f32_16x16x32_bf16 v[64:67], v[166:169], v[218:221], v[64:67]
	v_mfma_f32_16x16x32_bf16 v[170:173], v[178:181], v[218:221], v[170:173]
	ds_read_b128 v[218:221], v6 offset:10240
	s_waitcnt lgkmcnt(3)
	v_mfma_f32_16x16x32_bf16 v[72:75], v[158:161], v[222:225], v[72:75]
	v_mfma_f32_16x16x32_bf16 v[76:79], v[162:165], v[222:225], v[76:79]
	v_mfma_f32_16x16x32_bf16 v[80:83], v[166:169], v[222:225], v[80:83]
	v_mfma_f32_16x16x32_bf16 v[32:35], v[178:181], v[222:225], v[32:35]
	ds_read_b128 v[222:225], v6 offset:12288
	s_waitcnt lgkmcnt(3)
	v_mfma_f32_16x16x32_bf16 v[88:91], v[158:161], v[226:229], v[88:91]
	v_mfma_f32_16x16x32_bf16 v[92:95], v[162:165], v[226:229], v[92:95]
	v_mfma_f32_16x16x32_bf16 v[96:99], v[166:169], v[226:229], v[96:99]
	v_mfma_f32_16x16x32_bf16 v[36:39], v[178:181], v[226:229], v[36:39]
	ds_read_b128 v[226:229], v6 offset:14336
	s_waitcnt lgkmcnt(3)
	v_mfma_f32_16x16x32_bf16 v[104:107], v[158:161], v[214:217], v[104:107]
	v_mfma_f32_16x16x32_bf16 v[108:111], v[162:165], v[214:217], v[108:111]
	v_mfma_f32_16x16x32_bf16 v[112:115], v[166:169], v[214:217], v[112:115]
	v_mfma_f32_16x16x32_bf16 v[52:55], v[178:181], v[214:217], v[52:55]
	s_waitcnt lgkmcnt(2)
	v_mfma_f32_16x16x32_bf16 v[116:119], v[158:161], v[218:221], v[116:119]
	v_mfma_f32_16x16x32_bf16 v[120:123], v[162:165], v[218:221], v[120:123]
	v_mfma_f32_16x16x32_bf16 v[124:127], v[166:169], v[218:221], v[124:127]
	v_mfma_f32_16x16x32_bf16 v[68:71], v[178:181], v[218:221], v[68:71]
	s_waitcnt lgkmcnt(1)
	v_mfma_f32_16x16x32_bf16 v[132:135], v[162:165], v[222:225], v[132:135]
	v_mfma_f32_16x16x32_bf16 v[84:87], v[178:181], v[222:225], v[84:87]
	s_waitcnt lgkmcnt(0)
	v_mfma_f32_16x16x32_bf16 v[100:103], v[158:161], v[226:229], v[100:103]
	v_mfma_f32_16x16x32_bf16 v[150:153], v[166:169], v[226:229], v[150:153]
	v_mfma_f32_16x16x32_bf16 v[154:157], v[178:181], v[226:229], v[154:157]
	v_mfma_f32_16x16x32_bf16 v[128:131], v[158:161], v[222:225], v[128:131]
	v_mfma_f32_16x16x32_bf16 v[136:139], v[166:169], v[222:225], v[136:139]
	v_mfma_f32_16x16x32_bf16 v[140:143], v[162:165], v[226:229], v[140:143]
	ds_read_b128 v[158:161], v7 offset:33792
	ds_read_b128 v[162:165], v7 offset:35840
	ds_read_b128 v[166:169], v7 offset:37888
	ds_read_b128 v[214:217], v7 offset:39936
	ds_read_b128 v[178:181], v6 offset:1024
	ds_read_b128 v[218:221], v6 offset:3072
	ds_read_b128 v[222:225], v6 offset:5120
	ds_read_b128 v[226:229], v6 offset:7168
	s_waitcnt lgkmcnt(3)
	v_mfma_f32_16x16x32_bf16 v[40:43], v[158:161], v[178:181], v[40:43]
	v_mfma_f32_16x16x32_bf16 v[44:47], v[162:165], v[178:181], v[44:47]
	v_mfma_f32_16x16x32_bf16 v[48:51], v[166:169], v[178:181], v[48:51]
	v_mfma_f32_16x16x32_bf16 v[174:177], v[214:217], v[178:181], v[174:177]
	ds_read_b128 v[178:181], v6 offset:9216
	s_waitcnt lgkmcnt(3)
	v_mfma_f32_16x16x32_bf16 v[56:59], v[158:161], v[218:221], v[56:59]
	v_mfma_f32_16x16x32_bf16 v[60:63], v[162:165], v[218:221], v[60:63]
	v_mfma_f32_16x16x32_bf16 v[64:67], v[166:169], v[218:221], v[64:67]
	v_mfma_f32_16x16x32_bf16 v[170:173], v[214:217], v[218:221], v[170:173]
	ds_read_b128 v[218:221], v6 offset:11264
	s_waitcnt lgkmcnt(3)
	v_mfma_f32_16x16x32_bf16 v[72:75], v[158:161], v[222:225], v[72:75]
	v_mfma_f32_16x16x32_bf16 v[76:79], v[162:165], v[222:225], v[76:79]
	v_mfma_f32_16x16x32_bf16 v[80:83], v[166:169], v[222:225], v[80:83]
	v_mfma_f32_16x16x32_bf16 v[32:35], v[214:217], v[222:225], v[32:35]
	ds_read_b128 v[222:225], v6 offset:13312
	s_waitcnt lgkmcnt(3)
	v_mfma_f32_16x16x32_bf16 v[88:91], v[158:161], v[226:229], v[88:91]
	v_mfma_f32_16x16x32_bf16 v[92:95], v[162:165], v[226:229], v[92:95]
	v_mfma_f32_16x16x32_bf16 v[96:99], v[166:169], v[226:229], v[96:99]
	v_mfma_f32_16x16x32_bf16 v[36:39], v[214:217], v[226:229], v[36:39]
	ds_read_b128 v[226:229], v6 offset:15360
	s_waitcnt lgkmcnt(3)
	v_mfma_f32_16x16x32_bf16 v[104:107], v[158:161], v[178:181], v[104:107]
	v_mfma_f32_16x16x32_bf16 v[108:111], v[162:165], v[178:181], v[108:111]
	v_mfma_f32_16x16x32_bf16 v[112:115], v[166:169], v[178:181], v[112:115]
	v_mfma_f32_16x16x32_bf16 v[52:55], v[214:217], v[178:181], v[52:55]
	s_waitcnt lgkmcnt(2)
	v_mfma_f32_16x16x32_bf16 v[116:119], v[158:161], v[218:221], v[116:119]
	v_mfma_f32_16x16x32_bf16 v[120:123], v[162:165], v[218:221], v[120:123]
	v_mfma_f32_16x16x32_bf16 v[124:127], v[166:169], v[218:221], v[124:127]
	v_mfma_f32_16x16x32_bf16 v[68:71], v[214:217], v[218:221], v[68:71]
	s_waitcnt lgkmcnt(1)
	v_mfma_f32_16x16x32_bf16 v[132:135], v[162:165], v[222:225], v[132:135]
	v_mfma_f32_16x16x32_bf16 v[84:87], v[214:217], v[222:225], v[84:87]
	s_waitcnt lgkmcnt(0)
	v_mfma_f32_16x16x32_bf16 v[100:103], v[158:161], v[226:229], v[100:103]
	v_mfma_f32_16x16x32_bf16 v[150:153], v[166:169], v[226:229], v[150:153]
	v_mfma_f32_16x16x32_bf16 v[154:157], v[214:217], v[226:229], v[154:157]
	v_mfma_f32_16x16x32_bf16 v[128:131], v[158:161], v[222:225], v[128:131]
	v_mfma_f32_16x16x32_bf16 v[136:139], v[166:169], v[222:225], v[136:139]
	v_mfma_f32_16x16x32_bf16 v[140:143], v[162:165], v[226:229], v[140:143]
	s_add_u32 s64, s0, 0x200
	s_addc_u32 s65, s1, 0
	s_add_u32 s68, s14, 0x200
	s_waitcnt vmcnt(0)
	s_barrier
	s_addc_u32 s69, s15, 0
	ds_read_b128 v[158:161], v8
	ds_read_b128 v[162:165], v12
	ds_read_b128 v[166:169], v9
	ds_read_b128 v[178:181], v13
	ds_read_b128 v[214:217], v11
	ds_read_b128 v[218:221], v10
	ds_read_b128 v[222:225], v14
	ds_read_b128 v[226:229], v15
	s_waitcnt lgkmcnt(6)
	v_mfma_f32_16x16x32_bf16 v[40:43], v[158:161], v[162:165], v[40:43]
	s_waitcnt lgkmcnt(5)
	v_mfma_f32_16x16x32_bf16 v[44:47], v[166:169], v[162:165], v[44:47]
	s_waitcnt lgkmcnt(4)
	v_mfma_f32_16x16x32_bf16 v[56:59], v[158:161], v[178:181], v[56:59]
	s_mov_b32 m0, s42
	v_mfma_f32_16x16x32_bf16 v[60:63], v[166:169], v[178:181], v[60:63]
	global_load_lds_dwordx4 v0, s[64:65]
	s_waitcnt lgkmcnt(3)
	v_mfma_f32_16x16x32_bf16 v[48:51], v[214:217], v[162:165], v[48:51]
	v_mfma_f32_16x16x32_bf16 v[64:67], v[214:217], v[178:181], v[64:67]
	s_waitcnt lgkmcnt(2)
	v_mfma_f32_16x16x32_bf16 v[174:177], v[218:221], v[162:165], v[174:177]
	ds_read_b128 v[162:165], v16
	v_mfma_f32_16x16x32_bf16 v[170:173], v[218:221], v[178:181], v[170:173]
	ds_read_b128 v[178:181], v17
	s_waitcnt lgkmcnt(3)
	s_mov_b32 m0, s43
	v_mfma_f32_16x16x32_bf16 v[72:75], v[158:161], v[222:225], v[72:75]
	global_load_lds_dwordx4 v0, s[68:69]
	v_mfma_f32_16x16x32_bf16 v[76:79], v[166:169], v[222:225], v[76:79]
	v_mfma_f32_16x16x32_bf16 v[80:83], v[214:217], v[222:225], v[80:83]
	v_mfma_f32_16x16x32_bf16 v[32:35], v[218:221], v[222:225], v[32:35]
	ds_read_b128 v[222:225], v18
	s_waitcnt lgkmcnt(3)
	v_mfma_f32_16x16x32_bf16 v[88:91], v[158:161], v[226:229], v[88:91]
	s_mov_b32 m0, s44
	v_mfma_f32_16x16x32_bf16 v[92:95], v[166:169], v[226:229], v[92:95]
	global_load_lds_dwordx4 v2, s[64:65]
	v_mfma_f32_16x16x32_bf16 v[96:99], v[214:217], v[226:229], v[96:99]
	v_mfma_f32_16x16x32_bf16 v[36:39], v[218:221], v[226:229], v[36:39]
	ds_read_b128 v[226:229], v19
	s_waitcnt lgkmcnt(3)
	v_mfma_f32_16x16x32_bf16 v[104:107], v[158:161], v[162:165], v[104:107]
	s_waitcnt lgkmcnt(2)
	v_mfma_f32_16x16x32_bf16 v[116:119], v[158:161], v[178:181], v[116:119]
	s_waitcnt lgkmcnt(1)
	s_mov_b32 m0, s45
	v_mfma_f32_16x16x32_bf16 v[128:131], v[158:161], v[222:225], v[128:131]
	global_load_lds_dwordx4 v2, s[68:69]
	s_waitcnt lgkmcnt(0)
	v_mfma_f32_16x16x32_bf16 v[100:103], v[158:161], v[226:229], v[100:103]
	ds_read_b128 v[158:161], v20
	v_mfma_f32_16x16x32_bf16 v[108:111], v[166:169], v[162:165], v[108:111]
	v_mfma_f32_16x16x32_bf16 v[120:123], v[166:169], v[178:181], v[120:123]
	v_mfma_f32_16x16x32_bf16 v[132:135], v[166:169], v[222:225], v[132:135]
	s_mov_b32 m0, s46
	v_mfma_f32_16x16x32_bf16 v[140:143], v[166:169], v[226:229], v[140:143]
	global_load_lds_dwordx4 v4, s[64:65]
	ds_read_b128 v[166:169], v24
	v_mfma_f32_16x16x32_bf16 v[112:115], v[214:217], v[162:165], v[112:115]
	v_mfma_f32_16x16x32_bf16 v[52:55], v[218:221], v[162:165], v[52:55]
	ds_read_b128 v[162:165], v21
	v_mfma_f32_16x16x32_bf16 v[124:127], v[214:217], v[178:181], v[124:127]
	v_mfma_f32_16x16x32_bf16 v[68:71], v[218:221], v[178:181], v[68:71]
	ds_read_b128 v[178:181], v25
	s_mov_b32 m0, s47
	v_mfma_f32_16x16x32_bf16 v[136:139], v[214:217], v[222:225], v[136:139]
	global_load_lds_dwordx4 v4, s[68:69]
	v_mfma_f32_16x16x32_bf16 v[84:87], v[218:221], v[222:225], v[84:87]
	ds_read_b128 v[222:225], v26
	v_mfma_f32_16x16x32_bf16 v[150:153], v[214:217], v[226:229], v[150:153]
	ds_read_b128 v[214:217], v23
	v_mfma_f32_16x16x32_bf16 v[154:157], v[218:221], v[226:229], v[154:157]
	ds_read_b128 v[218:221], v22
	ds_read_b128 v[226:229], v27
	s_waitcnt lgkmcnt(6)
	v_mfma_f32_16x16x32_bf16 v[40:43], v[158:161], v[166:169], v[40:43]
	s_waitcnt lgkmcnt(5)
	s_mov_b32 m0, s49
	v_mfma_f32_16x16x32_bf16 v[44:47], v[162:165], v[166:169], v[44:47]
	global_load_lds_dwordx4 v146, s[64:65]
	s_waitcnt lgkmcnt(4)
	v_mfma_f32_16x16x32_bf16 v[56:59], v[158:161], v[178:181], v[56:59]
	v_mfma_f32_16x16x32_bf16 v[60:63], v[162:165], v[178:181], v[60:63]
	s_waitcnt lgkmcnt(3)
	v_mfma_f32_16x16x32_bf16 v[72:75], v[158:161], v[222:225], v[72:75]
	v_mfma_f32_16x16x32_bf16 v[76:79], v[162:165], v[222:225], v[76:79]
	s_waitcnt lgkmcnt(2)
	s_mov_b32 m0, s50
	v_mfma_f32_16x16x32_bf16 v[48:51], v[214:217], v[166:169], v[48:51]
	global_load_lds_dwordx4 v146, s[68:69]
	s_waitcnt lgkmcnt(1)
	v_mfma_f32_16x16x32_bf16 v[174:177], v[218:221], v[166:169], v[174:177]
	ds_read_b128 v[166:169], v28
	v_mfma_f32_16x16x32_bf16 v[64:67], v[214:217], v[178:181], v[64:67]
	v_mfma_f32_16x16x32_bf16 v[170:173], v[218:221], v[178:181], v[170:173]
	ds_read_b128 v[178:181], v29
	v_mfma_f32_16x16x32_bf16 v[80:83], v[214:217], v[222:225], v[80:83]
	v_mfma_f32_16x16x32_bf16 v[32:35], v[218:221], v[222:225], v[32:35]
	ds_read_b128 v[222:225], v30
	s_waitcnt lgkmcnt(3)
	v_mfma_f32_16x16x32_bf16 v[88:91], v[158:161], v[226:229], v[88:91]
	v_mfma_f32_16x16x32_bf16 v[92:95], v[162:165], v[226:229], v[92:95]
	v_mfma_f32_16x16x32_bf16 v[96:99], v[214:217], v[226:229], v[96:99]
	v_mfma_f32_16x16x32_bf16 v[36:39], v[218:221], v[226:229], v[36:39]
	ds_read_b128 v[226:229], v31
	s_waitcnt lgkmcnt(3)
	v_mfma_f32_16x16x32_bf16 v[104:107], v[158:161], v[166:169], v[104:107]
	v_mfma_f32_16x16x32_bf16 v[108:111], v[162:165], v[166:169], v[108:111]
	v_mfma_f32_16x16x32_bf16 v[112:115], v[214:217], v[166:169], v[112:115]
	v_mfma_f32_16x16x32_bf16 v[52:55], v[218:221], v[166:169], v[52:55]
	s_waitcnt lgkmcnt(2)
	v_mfma_f32_16x16x32_bf16 v[116:119], v[158:161], v[178:181], v[116:119]
	v_mfma_f32_16x16x32_bf16 v[120:123], v[162:165], v[178:181], v[120:123]
	v_mfma_f32_16x16x32_bf16 v[124:127], v[214:217], v[178:181], v[124:127]
	v_mfma_f32_16x16x32_bf16 v[68:71], v[218:221], v[178:181], v[68:71]
	s_waitcnt lgkmcnt(1)
	v_mfma_f32_16x16x32_bf16 v[128:131], v[158:161], v[222:225], v[128:131]
	v_mfma_f32_16x16x32_bf16 v[132:135], v[162:165], v[222:225], v[132:135]
	v_mfma_f32_16x16x32_bf16 v[136:139], v[214:217], v[222:225], v[136:139]
	v_mfma_f32_16x16x32_bf16 v[84:87], v[218:221], v[222:225], v[84:87]
	s_waitcnt lgkmcnt(0)
	v_mfma_f32_16x16x32_bf16 v[100:103], v[158:161], v[226:229], v[100:103]
	v_mfma_f32_16x16x32_bf16 v[140:143], v[162:165], v[226:229], v[140:143]
	v_mfma_f32_16x16x32_bf16 v[150:153], v[214:217], v[226:229], v[150:153]
	v_mfma_f32_16x16x32_bf16 v[154:157], v[218:221], v[226:229], v[154:157]
	s_add_u32 s64, s0, 0x280
	s_addc_u32 s65, s1, 0
	s_add_u32 s68, s14, 0x280
	s_waitcnt vmcnt(0)
	s_barrier
	s_addc_u32 s69, s15, 0
	ds_read_b128 v[158:161], v7 offset:32768
	ds_read_b128 v[162:165], v6
	ds_read_b128 v[166:169], v7 offset:34816
	ds_read_b128 v[178:181], v6 offset:2048
	ds_read_b128 v[214:217], v7 offset:36864
	ds_read_b128 v[218:221], v7 offset:38912
	ds_read_b128 v[222:225], v6 offset:4096
	ds_read_b128 v[226:229], v6 offset:6144
	s_waitcnt lgkmcnt(6)
	v_mfma_f32_16x16x32_bf16 v[40:43], v[158:161], v[162:165], v[40:43]
	s_waitcnt lgkmcnt(5)
	v_mfma_f32_16x16x32_bf16 v[44:47], v[166:169], v[162:165], v[44:47]
	s_waitcnt lgkmcnt(4)
	v_mfma_f32_16x16x32_bf16 v[56:59], v[158:161], v[178:181], v[56:59]
	s_mov_b32 m0, s52
	v_mfma_f32_16x16x32_bf16 v[60:63], v[166:169], v[178:181], v[60:63]
	global_load_lds_dwordx4 v0, s[64:65]
	s_waitcnt lgkmcnt(3)
	v_mfma_f32_16x16x32_bf16 v[48:51], v[214:217], v[162:165], v[48:51]
	v_mfma_f32_16x16x32_bf16 v[64:67], v[214:217], v[178:181], v[64:67]
	s_waitcnt lgkmcnt(2)
	v_mfma_f32_16x16x32_bf16 v[174:177], v[218:221], v[162:165], v[174:177]
	ds_read_b128 v[162:165], v6 offset:8192
	v_mfma_f32_16x16x32_bf16 v[170:173], v[218:221], v[178:181], v[170:173]
	ds_read_b128 v[178:181], v6 offset:10240
	s_waitcnt lgkmcnt(3)
	s_mov_b32 m0, s51
	v_mfma_f32_16x16x32_bf16 v[72:75], v[158:161], v[222:225], v[72:75]
	global_load_lds_dwordx4 v0, s[68:69]
	v_mfma_f32_16x16x32_bf16 v[76:79], v[166:169], v[222:225], v[76:79]
	v_mfma_f32_16x16x32_bf16 v[80:83], v[214:217], v[222:225], v[80:83]
	v_mfma_f32_16x16x32_bf16 v[32:35], v[218:221], v[222:225], v[32:35]
	ds_read_b128 v[222:225], v6 offset:12288
	s_waitcnt lgkmcnt(3)
	v_mfma_f32_16x16x32_bf16 v[88:91], v[158:161], v[226:229], v[88:91]
	s_mov_b32 m0, s53
	v_mfma_f32_16x16x32_bf16 v[92:95], v[166:169], v[226:229], v[92:95]
	global_load_lds_dwordx4 v2, s[64:65]
	v_mfma_f32_16x16x32_bf16 v[96:99], v[214:217], v[226:229], v[96:99]
	v_mfma_f32_16x16x32_bf16 v[36:39], v[218:221], v[226:229], v[36:39]
	ds_read_b128 v[226:229], v6 offset:14336
	s_waitcnt lgkmcnt(3)
	v_mfma_f32_16x16x32_bf16 v[104:107], v[158:161], v[162:165], v[104:107]
	s_waitcnt lgkmcnt(2)
	v_mfma_f32_16x16x32_bf16 v[116:119], v[158:161], v[178:181], v[116:119]
	s_waitcnt lgkmcnt(1)
	s_mov_b32 m0, s54
	v_mfma_f32_16x16x32_bf16 v[128:131], v[158:161], v[222:225], v[128:131]
	global_load_lds_dwordx4 v2, s[68:69]
	s_waitcnt lgkmcnt(0)
	v_mfma_f32_16x16x32_bf16 v[100:103], v[158:161], v[226:229], v[100:103]
	ds_read_b128 v[158:161], v7 offset:33792
	v_mfma_f32_16x16x32_bf16 v[108:111], v[166:169], v[162:165], v[108:111]
	v_mfma_f32_16x16x32_bf16 v[120:123], v[166:169], v[178:181], v[120:123]
	v_mfma_f32_16x16x32_bf16 v[132:135], v[166:169], v[222:225], v[132:135]
	s_mov_b32 m0, s55
	v_mfma_f32_16x16x32_bf16 v[140:143], v[166:169], v[226:229], v[140:143]
	global_load_lds_dwordx4 v4, s[64:65]
	ds_read_b128 v[166:169], v6 offset:1024
	v_mfma_f32_16x16x32_bf16 v[112:115], v[214:217], v[162:165], v[112:115]
	v_mfma_f32_16x16x32_bf16 v[52:55], v[218:221], v[162:165], v[52:55]
	ds_read_b128 v[162:165], v7 offset:35840
	v_mfma_f32_16x16x32_bf16 v[124:127], v[214:217], v[178:181], v[124:127]
	v_mfma_f32_16x16x32_bf16 v[68:71], v[218:221], v[178:181], v[68:71]
	ds_read_b128 v[178:181], v6 offset:3072
	s_mov_b32 m0, s58
	v_mfma_f32_16x16x32_bf16 v[136:139], v[214:217], v[222:225], v[136:139]
	global_load_lds_dwordx4 v4, s[68:69]
	v_mfma_f32_16x16x32_bf16 v[84:87], v[218:221], v[222:225], v[84:87]
	ds_read_b128 v[222:225], v6 offset:5120
	v_mfma_f32_16x16x32_bf16 v[150:153], v[214:217], v[226:229], v[150:153]
	ds_read_b128 v[214:217], v7 offset:37888
	v_mfma_f32_16x16x32_bf16 v[154:157], v[218:221], v[226:229], v[154:157]
	ds_read_b128 v[218:221], v7 offset:39936
	ds_read_b128 v[226:229], v6 offset:7168
	s_waitcnt lgkmcnt(6)
	v_mfma_f32_16x16x32_bf16 v[40:43], v[158:161], v[166:169], v[40:43]
	s_waitcnt lgkmcnt(5)
	s_mov_b32 m0, s62
	v_mfma_f32_16x16x32_bf16 v[44:47], v[162:165], v[166:169], v[44:47]
	global_load_lds_dwordx4 v146, s[64:65]
	s_waitcnt lgkmcnt(4)
	v_mfma_f32_16x16x32_bf16 v[56:59], v[158:161], v[178:181], v[56:59]
	v_mfma_f32_16x16x32_bf16 v[60:63], v[162:165], v[178:181], v[60:63]
	s_waitcnt lgkmcnt(3)
	v_mfma_f32_16x16x32_bf16 v[72:75], v[158:161], v[222:225], v[72:75]
	v_mfma_f32_16x16x32_bf16 v[76:79], v[162:165], v[222:225], v[76:79]
	s_waitcnt lgkmcnt(2)
	s_mov_b32 m0, s63
	v_mfma_f32_16x16x32_bf16 v[48:51], v[214:217], v[166:169], v[48:51]
	global_load_lds_dwordx4 v146, s[68:69]
	s_waitcnt lgkmcnt(1)
	v_mfma_f32_16x16x32_bf16 v[174:177], v[218:221], v[166:169], v[174:177]
	ds_read_b128 v[166:169], v6 offset:9216
	v_mfma_f32_16x16x32_bf16 v[64:67], v[214:217], v[178:181], v[64:67]
	v_mfma_f32_16x16x32_bf16 v[170:173], v[218:221], v[178:181], v[170:173]
	ds_read_b128 v[178:181], v6 offset:11264
	v_mfma_f32_16x16x32_bf16 v[80:83], v[214:217], v[222:225], v[80:83]
	v_mfma_f32_16x16x32_bf16 v[32:35], v[218:221], v[222:225], v[32:35]
	ds_read_b128 v[222:225], v6 offset:13312
	s_waitcnt lgkmcnt(3)
	v_mfma_f32_16x16x32_bf16 v[88:91], v[158:161], v[226:229], v[88:91]
	v_mfma_f32_16x16x32_bf16 v[92:95], v[162:165], v[226:229], v[92:95]
	v_mfma_f32_16x16x32_bf16 v[96:99], v[214:217], v[226:229], v[96:99]
	v_mfma_f32_16x16x32_bf16 v[36:39], v[218:221], v[226:229], v[36:39]
	ds_read_b128 v[226:229], v6 offset:15360
	s_waitcnt lgkmcnt(3)
	v_mfma_f32_16x16x32_bf16 v[104:107], v[158:161], v[166:169], v[104:107]
	v_mfma_f32_16x16x32_bf16 v[108:111], v[162:165], v[166:169], v[108:111]
	v_mfma_f32_16x16x32_bf16 v[112:115], v[214:217], v[166:169], v[112:115]
	v_mfma_f32_16x16x32_bf16 v[52:55], v[218:221], v[166:169], v[52:55]
	s_waitcnt lgkmcnt(2)
	v_mfma_f32_16x16x32_bf16 v[116:119], v[158:161], v[178:181], v[116:119]
	v_mfma_f32_16x16x32_bf16 v[120:123], v[162:165], v[178:181], v[120:123]
	v_mfma_f32_16x16x32_bf16 v[124:127], v[214:217], v[178:181], v[124:127]
	v_mfma_f32_16x16x32_bf16 v[68:71], v[218:221], v[178:181], v[68:71]
	s_waitcnt lgkmcnt(1)
	v_mfma_f32_16x16x32_bf16 v[128:131], v[158:161], v[222:225], v[128:131]
	v_mfma_f32_16x16x32_bf16 v[132:135], v[162:165], v[222:225], v[132:135]
	v_mfma_f32_16x16x32_bf16 v[136:139], v[214:217], v[222:225], v[136:139]
	v_mfma_f32_16x16x32_bf16 v[84:87], v[218:221], v[222:225], v[84:87]
	s_waitcnt lgkmcnt(0)
	v_mfma_f32_16x16x32_bf16 v[100:103], v[158:161], v[226:229], v[100:103]
	v_mfma_f32_16x16x32_bf16 v[140:143], v[162:165], v[226:229], v[140:143]
	v_mfma_f32_16x16x32_bf16 v[150:153], v[214:217], v[226:229], v[150:153]
	v_mfma_f32_16x16x32_bf16 v[154:157], v[218:221], v[226:229], v[154:157]
	s_add_u32 s64, s0, 0x300
	s_addc_u32 s65, s1, 0
	s_add_u32 s68, s14, 0x300
	s_waitcnt vmcnt(0)
	s_barrier
	s_addc_u32 s69, s15, 0
	ds_read_b128 v[158:161], v8
	ds_read_b128 v[162:165], v12
	ds_read_b128 v[166:169], v9
	ds_read_b128 v[178:181], v13
	ds_read_b128 v[214:217], v11
	ds_read_b128 v[218:221], v10
	ds_read_b128 v[222:225], v14
	ds_read_b128 v[226:229], v15
	s_waitcnt lgkmcnt(6)
	v_mfma_f32_16x16x32_bf16 v[40:43], v[158:161], v[162:165], v[40:43]
	s_waitcnt lgkmcnt(5)
	v_mfma_f32_16x16x32_bf16 v[44:47], v[166:169], v[162:165], v[44:47]
	s_waitcnt lgkmcnt(4)
	v_mfma_f32_16x16x32_bf16 v[56:59], v[158:161], v[178:181], v[56:59]
	s_mov_b32 m0, s42
	v_mfma_f32_16x16x32_bf16 v[60:63], v[166:169], v[178:181], v[60:63]
	global_load_lds_dwordx4 v0, s[64:65]
	s_waitcnt lgkmcnt(3)
	v_mfma_f32_16x16x32_bf16 v[48:51], v[214:217], v[162:165], v[48:51]
	v_mfma_f32_16x16x32_bf16 v[64:67], v[214:217], v[178:181], v[64:67]
	s_waitcnt lgkmcnt(2)
	v_mfma_f32_16x16x32_bf16 v[174:177], v[218:221], v[162:165], v[174:177]
	ds_read_b128 v[162:165], v16
	v_mfma_f32_16x16x32_bf16 v[170:173], v[218:221], v[178:181], v[170:173]
	ds_read_b128 v[178:181], v17
	s_waitcnt lgkmcnt(3)
	s_mov_b32 m0, s43
	v_mfma_f32_16x16x32_bf16 v[72:75], v[158:161], v[222:225], v[72:75]
	global_load_lds_dwordx4 v0, s[68:69]
	v_mfma_f32_16x16x32_bf16 v[76:79], v[166:169], v[222:225], v[76:79]
	v_mfma_f32_16x16x32_bf16 v[80:83], v[214:217], v[222:225], v[80:83]
	v_mfma_f32_16x16x32_bf16 v[32:35], v[218:221], v[222:225], v[32:35]
	ds_read_b128 v[222:225], v18
	s_waitcnt lgkmcnt(3)
	v_mfma_f32_16x16x32_bf16 v[88:91], v[158:161], v[226:229], v[88:91]
	s_mov_b32 m0, s44
	v_mfma_f32_16x16x32_bf16 v[92:95], v[166:169], v[226:229], v[92:95]
	global_load_lds_dwordx4 v2, s[64:65]
	v_mfma_f32_16x16x32_bf16 v[96:99], v[214:217], v[226:229], v[96:99]
	v_mfma_f32_16x16x32_bf16 v[36:39], v[218:221], v[226:229], v[36:39]
	ds_read_b128 v[226:229], v19
	s_waitcnt lgkmcnt(3)
	v_mfma_f32_16x16x32_bf16 v[104:107], v[158:161], v[162:165], v[104:107]
	s_waitcnt lgkmcnt(2)
	v_mfma_f32_16x16x32_bf16 v[116:119], v[158:161], v[178:181], v[116:119]
	s_waitcnt lgkmcnt(1)
	s_mov_b32 m0, s45
	v_mfma_f32_16x16x32_bf16 v[128:131], v[158:161], v[222:225], v[128:131]
	global_load_lds_dwordx4 v2, s[68:69]
	s_waitcnt lgkmcnt(0)
	v_mfma_f32_16x16x32_bf16 v[100:103], v[158:161], v[226:229], v[100:103]
	ds_read_b128 v[158:161], v20
	v_mfma_f32_16x16x32_bf16 v[108:111], v[166:169], v[162:165], v[108:111]
	v_mfma_f32_16x16x32_bf16 v[120:123], v[166:169], v[178:181], v[120:123]
	v_mfma_f32_16x16x32_bf16 v[132:135], v[166:169], v[222:225], v[132:135]
	s_mov_b32 m0, s46
	v_mfma_f32_16x16x32_bf16 v[140:143], v[166:169], v[226:229], v[140:143]
	global_load_lds_dwordx4 v4, s[64:65]
	ds_read_b128 v[166:169], v24
	v_mfma_f32_16x16x32_bf16 v[112:115], v[214:217], v[162:165], v[112:115]
	v_mfma_f32_16x16x32_bf16 v[52:55], v[218:221], v[162:165], v[52:55]
	ds_read_b128 v[162:165], v21
	v_mfma_f32_16x16x32_bf16 v[124:127], v[214:217], v[178:181], v[124:127]
	v_mfma_f32_16x16x32_bf16 v[68:71], v[218:221], v[178:181], v[68:71]
	ds_read_b128 v[178:181], v25
	s_mov_b32 m0, s47
	v_mfma_f32_16x16x32_bf16 v[136:139], v[214:217], v[222:225], v[136:139]
	global_load_lds_dwordx4 v4, s[68:69]
	v_mfma_f32_16x16x32_bf16 v[84:87], v[218:221], v[222:225], v[84:87]
	ds_read_b128 v[222:225], v26
	v_mfma_f32_16x16x32_bf16 v[150:153], v[214:217], v[226:229], v[150:153]
	ds_read_b128 v[214:217], v23
	v_mfma_f32_16x16x32_bf16 v[154:157], v[218:221], v[226:229], v[154:157]
	ds_read_b128 v[218:221], v22
	ds_read_b128 v[226:229], v27
	s_waitcnt lgkmcnt(6)
	v_mfma_f32_16x16x32_bf16 v[40:43], v[158:161], v[166:169], v[40:43]
	s_waitcnt lgkmcnt(5)
	s_mov_b32 m0, s49
	v_mfma_f32_16x16x32_bf16 v[44:47], v[162:165], v[166:169], v[44:47]
	global_load_lds_dwordx4 v146, s[64:65]
	s_waitcnt lgkmcnt(4)
	v_mfma_f32_16x16x32_bf16 v[56:59], v[158:161], v[178:181], v[56:59]
	v_mfma_f32_16x16x32_bf16 v[60:63], v[162:165], v[178:181], v[60:63]
	s_waitcnt lgkmcnt(3)
	v_mfma_f32_16x16x32_bf16 v[72:75], v[158:161], v[222:225], v[72:75]
	v_mfma_f32_16x16x32_bf16 v[76:79], v[162:165], v[222:225], v[76:79]
	s_waitcnt lgkmcnt(2)
	s_mov_b32 m0, s50
	v_mfma_f32_16x16x32_bf16 v[48:51], v[214:217], v[166:169], v[48:51]
	global_load_lds_dwordx4 v146, s[68:69]
	s_waitcnt lgkmcnt(1)
	v_mfma_f32_16x16x32_bf16 v[174:177], v[218:221], v[166:169], v[174:177]
	ds_read_b128 v[166:169], v28
	v_mfma_f32_16x16x32_bf16 v[64:67], v[214:217], v[178:181], v[64:67]
	v_mfma_f32_16x16x32_bf16 v[170:173], v[218:221], v[178:181], v[170:173]
	ds_read_b128 v[178:181], v29
	v_mfma_f32_16x16x32_bf16 v[80:83], v[214:217], v[222:225], v[80:83]
	v_mfma_f32_16x16x32_bf16 v[32:35], v[218:221], v[222:225], v[32:35]
	ds_read_b128 v[222:225], v30
	s_waitcnt lgkmcnt(3)
	v_mfma_f32_16x16x32_bf16 v[88:91], v[158:161], v[226:229], v[88:91]
	v_mfma_f32_16x16x32_bf16 v[92:95], v[162:165], v[226:229], v[92:95]
	v_mfma_f32_16x16x32_bf16 v[96:99], v[214:217], v[226:229], v[96:99]
	v_mfma_f32_16x16x32_bf16 v[36:39], v[218:221], v[226:229], v[36:39]
	ds_read_b128 v[226:229], v31
	s_waitcnt lgkmcnt(3)
	v_mfma_f32_16x16x32_bf16 v[104:107], v[158:161], v[166:169], v[104:107]
	v_mfma_f32_16x16x32_bf16 v[108:111], v[162:165], v[166:169], v[108:111]
	v_mfma_f32_16x16x32_bf16 v[112:115], v[214:217], v[166:169], v[112:115]
	v_mfma_f32_16x16x32_bf16 v[52:55], v[218:221], v[166:169], v[52:55]
	s_waitcnt lgkmcnt(2)
	v_mfma_f32_16x16x32_bf16 v[116:119], v[158:161], v[178:181], v[116:119]
	v_mfma_f32_16x16x32_bf16 v[120:123], v[162:165], v[178:181], v[120:123]
	v_mfma_f32_16x16x32_bf16 v[124:127], v[214:217], v[178:181], v[124:127]
	v_mfma_f32_16x16x32_bf16 v[68:71], v[218:221], v[178:181], v[68:71]
	s_waitcnt lgkmcnt(1)
	v_mfma_f32_16x16x32_bf16 v[128:131], v[158:161], v[222:225], v[128:131]
	v_mfma_f32_16x16x32_bf16 v[132:135], v[162:165], v[222:225], v[132:135]
	v_mfma_f32_16x16x32_bf16 v[136:139], v[214:217], v[222:225], v[136:139]
	v_mfma_f32_16x16x32_bf16 v[84:87], v[218:221], v[222:225], v[84:87]
	s_waitcnt lgkmcnt(0)
	v_mfma_f32_16x16x32_bf16 v[100:103], v[158:161], v[226:229], v[100:103]
	v_mfma_f32_16x16x32_bf16 v[140:143], v[162:165], v[226:229], v[140:143]
	v_mfma_f32_16x16x32_bf16 v[150:153], v[214:217], v[226:229], v[150:153]
	v_mfma_f32_16x16x32_bf16 v[154:157], v[218:221], v[226:229], v[154:157]
	s_add_u32 s64, s0, 0x380
	s_addc_u32 s65, s1, 0
	s_add_u32 s68, s14, 0x380
	s_waitcnt vmcnt(0)
	s_barrier
	s_addc_u32 s69, s15, 0
	ds_read_b128 v[158:161], v7 offset:32768
	ds_read_b128 v[162:165], v6
	ds_read_b128 v[166:169], v7 offset:34816
	ds_read_b128 v[178:181], v6 offset:2048
	ds_read_b128 v[214:217], v7 offset:36864
	ds_read_b128 v[218:221], v7 offset:38912
	ds_read_b128 v[222:225], v6 offset:4096
	ds_read_b128 v[226:229], v6 offset:6144
	s_waitcnt lgkmcnt(6)
	v_mfma_f32_16x16x32_bf16 v[40:43], v[158:161], v[162:165], v[40:43]
	s_waitcnt lgkmcnt(5)
	v_mfma_f32_16x16x32_bf16 v[44:47], v[166:169], v[162:165], v[44:47]
	s_waitcnt lgkmcnt(4)
	v_mfma_f32_16x16x32_bf16 v[56:59], v[158:161], v[178:181], v[56:59]
	s_mov_b32 m0, s52
	v_mfma_f32_16x16x32_bf16 v[60:63], v[166:169], v[178:181], v[60:63]
	global_load_lds_dwordx4 v0, s[64:65]
	s_waitcnt lgkmcnt(3)
	v_mfma_f32_16x16x32_bf16 v[48:51], v[214:217], v[162:165], v[48:51]
	v_mfma_f32_16x16x32_bf16 v[64:67], v[214:217], v[178:181], v[64:67]
	s_waitcnt lgkmcnt(2)
	v_mfma_f32_16x16x32_bf16 v[174:177], v[218:221], v[162:165], v[174:177]
	ds_read_b128 v[162:165], v6 offset:8192
	v_mfma_f32_16x16x32_bf16 v[170:173], v[218:221], v[178:181], v[170:173]
	ds_read_b128 v[178:181], v6 offset:10240
	s_waitcnt lgkmcnt(3)
	s_mov_b32 m0, s51
	v_mfma_f32_16x16x32_bf16 v[72:75], v[158:161], v[222:225], v[72:75]
	global_load_lds_dwordx4 v0, s[68:69]
	v_mfma_f32_16x16x32_bf16 v[76:79], v[166:169], v[222:225], v[76:79]
	v_mfma_f32_16x16x32_bf16 v[80:83], v[214:217], v[222:225], v[80:83]
	v_mfma_f32_16x16x32_bf16 v[32:35], v[218:221], v[222:225], v[32:35]
	ds_read_b128 v[222:225], v6 offset:12288
	s_waitcnt lgkmcnt(3)
	v_mfma_f32_16x16x32_bf16 v[88:91], v[158:161], v[226:229], v[88:91]
	s_mov_b32 m0, s53
	v_mfma_f32_16x16x32_bf16 v[92:95], v[166:169], v[226:229], v[92:95]
	global_load_lds_dwordx4 v2, s[64:65]
	v_mfma_f32_16x16x32_bf16 v[96:99], v[214:217], v[226:229], v[96:99]
	v_mfma_f32_16x16x32_bf16 v[36:39], v[218:221], v[226:229], v[36:39]
	ds_read_b128 v[226:229], v6 offset:14336
	s_waitcnt lgkmcnt(3)
	v_mfma_f32_16x16x32_bf16 v[104:107], v[158:161], v[162:165], v[104:107]
	s_waitcnt lgkmcnt(2)
	v_mfma_f32_16x16x32_bf16 v[116:119], v[158:161], v[178:181], v[116:119]
	s_waitcnt lgkmcnt(1)
	s_mov_b32 m0, s54
	v_mfma_f32_16x16x32_bf16 v[128:131], v[158:161], v[222:225], v[128:131]
	global_load_lds_dwordx4 v2, s[68:69]
	s_waitcnt lgkmcnt(0)
	v_mfma_f32_16x16x32_bf16 v[100:103], v[158:161], v[226:229], v[100:103]
	ds_read_b128 v[158:161], v7 offset:33792
	v_mfma_f32_16x16x32_bf16 v[108:111], v[166:169], v[162:165], v[108:111]
	v_mfma_f32_16x16x32_bf16 v[120:123], v[166:169], v[178:181], v[120:123]
	v_mfma_f32_16x16x32_bf16 v[132:135], v[166:169], v[222:225], v[132:135]
	s_mov_b32 m0, s55
	v_mfma_f32_16x16x32_bf16 v[140:143], v[166:169], v[226:229], v[140:143]
	global_load_lds_dwordx4 v4, s[64:65]
	ds_read_b128 v[166:169], v6 offset:1024
	v_mfma_f32_16x16x32_bf16 v[112:115], v[214:217], v[162:165], v[112:115]
	v_mfma_f32_16x16x32_bf16 v[52:55], v[218:221], v[162:165], v[52:55]
	ds_read_b128 v[162:165], v7 offset:35840
	v_mfma_f32_16x16x32_bf16 v[124:127], v[214:217], v[178:181], v[124:127]
	v_mfma_f32_16x16x32_bf16 v[68:71], v[218:221], v[178:181], v[68:71]
	ds_read_b128 v[178:181], v6 offset:3072
	s_mov_b32 m0, s58
	v_mfma_f32_16x16x32_bf16 v[136:139], v[214:217], v[222:225], v[136:139]
	global_load_lds_dwordx4 v4, s[68:69]
	v_mfma_f32_16x16x32_bf16 v[84:87], v[218:221], v[222:225], v[84:87]
	ds_read_b128 v[222:225], v6 offset:5120
	v_mfma_f32_16x16x32_bf16 v[150:153], v[214:217], v[226:229], v[150:153]
	ds_read_b128 v[214:217], v7 offset:37888
	v_mfma_f32_16x16x32_bf16 v[154:157], v[218:221], v[226:229], v[154:157]
	ds_read_b128 v[218:221], v7 offset:39936
	ds_read_b128 v[226:229], v6 offset:7168
	s_waitcnt lgkmcnt(6)
	v_mfma_f32_16x16x32_bf16 v[40:43], v[158:161], v[166:169], v[40:43]
	s_waitcnt lgkmcnt(5)
	s_mov_b32 m0, s62
	v_mfma_f32_16x16x32_bf16 v[44:47], v[162:165], v[166:169], v[44:47]
	global_load_lds_dwordx4 v146, s[64:65]
	s_waitcnt lgkmcnt(4)
	v_mfma_f32_16x16x32_bf16 v[56:59], v[158:161], v[178:181], v[56:59]
	v_mfma_f32_16x16x32_bf16 v[60:63], v[162:165], v[178:181], v[60:63]
	s_waitcnt lgkmcnt(3)
	v_mfma_f32_16x16x32_bf16 v[72:75], v[158:161], v[222:225], v[72:75]
	v_mfma_f32_16x16x32_bf16 v[76:79], v[162:165], v[222:225], v[76:79]
	s_waitcnt lgkmcnt(2)
	s_mov_b32 m0, s63
	v_mfma_f32_16x16x32_bf16 v[48:51], v[214:217], v[166:169], v[48:51]
	global_load_lds_dwordx4 v146, s[68:69]
	s_waitcnt lgkmcnt(1)
	v_mfma_f32_16x16x32_bf16 v[174:177], v[218:221], v[166:169], v[174:177]
	ds_read_b128 v[166:169], v6 offset:9216
	v_mfma_f32_16x16x32_bf16 v[64:67], v[214:217], v[178:181], v[64:67]
	v_mfma_f32_16x16x32_bf16 v[170:173], v[218:221], v[178:181], v[170:173]
	ds_read_b128 v[178:181], v6 offset:11264
	v_mfma_f32_16x16x32_bf16 v[80:83], v[214:217], v[222:225], v[80:83]
	v_mfma_f32_16x16x32_bf16 v[32:35], v[218:221], v[222:225], v[32:35]
	ds_read_b128 v[222:225], v6 offset:13312
	s_waitcnt lgkmcnt(3)
	v_mfma_f32_16x16x32_bf16 v[88:91], v[158:161], v[226:229], v[88:91]
	v_mfma_f32_16x16x32_bf16 v[92:95], v[162:165], v[226:229], v[92:95]
	v_mfma_f32_16x16x32_bf16 v[96:99], v[214:217], v[226:229], v[96:99]
	v_mfma_f32_16x16x32_bf16 v[36:39], v[218:221], v[226:229], v[36:39]
	ds_read_b128 v[226:229], v6 offset:15360
	s_waitcnt lgkmcnt(3)
	v_mfma_f32_16x16x32_bf16 v[104:107], v[158:161], v[166:169], v[104:107]
	v_mfma_f32_16x16x32_bf16 v[108:111], v[162:165], v[166:169], v[108:111]
	v_mfma_f32_16x16x32_bf16 v[112:115], v[214:217], v[166:169], v[112:115]
	v_mfma_f32_16x16x32_bf16 v[52:55], v[218:221], v[166:169], v[52:55]
	s_waitcnt lgkmcnt(2)
	v_mfma_f32_16x16x32_bf16 v[116:119], v[158:161], v[178:181], v[116:119]
	v_mfma_f32_16x16x32_bf16 v[120:123], v[162:165], v[178:181], v[120:123]
	v_mfma_f32_16x16x32_bf16 v[124:127], v[214:217], v[178:181], v[124:127]
	v_mfma_f32_16x16x32_bf16 v[68:71], v[218:221], v[178:181], v[68:71]
	s_waitcnt lgkmcnt(1)
	v_mfma_f32_16x16x32_bf16 v[128:131], v[158:161], v[222:225], v[128:131]
	v_mfma_f32_16x16x32_bf16 v[132:135], v[162:165], v[222:225], v[132:135]
	v_mfma_f32_16x16x32_bf16 v[136:139], v[214:217], v[222:225], v[136:139]
	v_mfma_f32_16x16x32_bf16 v[84:87], v[218:221], v[222:225], v[84:87]
	s_waitcnt lgkmcnt(0)
	v_mfma_f32_16x16x32_bf16 v[100:103], v[158:161], v[226:229], v[100:103]
	v_mfma_f32_16x16x32_bf16 v[140:143], v[162:165], v[226:229], v[140:143]
	v_mfma_f32_16x16x32_bf16 v[150:153], v[214:217], v[226:229], v[150:153]
	v_mfma_f32_16x16x32_bf16 v[154:157], v[218:221], v[226:229], v[154:157]
	s_add_u32 s64, s0, 0x400
	s_addc_u32 s65, s1, 0
	s_add_u32 s68, s14, 0x400
	s_waitcnt vmcnt(0)
	s_barrier
	s_addc_u32 s69, s15, 0
	ds_read_b128 v[158:161], v8
	ds_read_b128 v[162:165], v12
	ds_read_b128 v[166:169], v9
	ds_read_b128 v[178:181], v13
	ds_read_b128 v[214:217], v11
	ds_read_b128 v[218:221], v10
	ds_read_b128 v[222:225], v14
	ds_read_b128 v[226:229], v15
	s_waitcnt lgkmcnt(6)
	v_mfma_f32_16x16x32_bf16 v[40:43], v[158:161], v[162:165], v[40:43]
	s_waitcnt lgkmcnt(5)
	v_mfma_f32_16x16x32_bf16 v[44:47], v[166:169], v[162:165], v[44:47]
	s_waitcnt lgkmcnt(4)
	v_mfma_f32_16x16x32_bf16 v[56:59], v[158:161], v[178:181], v[56:59]
	s_mov_b32 m0, s42
	v_mfma_f32_16x16x32_bf16 v[60:63], v[166:169], v[178:181], v[60:63]
	global_load_lds_dwordx4 v0, s[64:65]
	s_waitcnt lgkmcnt(3)
	v_mfma_f32_16x16x32_bf16 v[48:51], v[214:217], v[162:165], v[48:51]
	v_mfma_f32_16x16x32_bf16 v[64:67], v[214:217], v[178:181], v[64:67]
	s_waitcnt lgkmcnt(2)
	v_mfma_f32_16x16x32_bf16 v[174:177], v[218:221], v[162:165], v[174:177]
	ds_read_b128 v[162:165], v16
	v_mfma_f32_16x16x32_bf16 v[170:173], v[218:221], v[178:181], v[170:173]
	ds_read_b128 v[178:181], v17
	s_waitcnt lgkmcnt(3)
	s_mov_b32 m0, s43
	v_mfma_f32_16x16x32_bf16 v[72:75], v[158:161], v[222:225], v[72:75]
	global_load_lds_dwordx4 v0, s[68:69]
	v_mfma_f32_16x16x32_bf16 v[76:79], v[166:169], v[222:225], v[76:79]
	v_mfma_f32_16x16x32_bf16 v[80:83], v[214:217], v[222:225], v[80:83]
	v_mfma_f32_16x16x32_bf16 v[32:35], v[218:221], v[222:225], v[32:35]
	ds_read_b128 v[222:225], v18
	s_waitcnt lgkmcnt(3)
	v_mfma_f32_16x16x32_bf16 v[88:91], v[158:161], v[226:229], v[88:91]
	s_mov_b32 m0, s44
	v_mfma_f32_16x16x32_bf16 v[92:95], v[166:169], v[226:229], v[92:95]
	global_load_lds_dwordx4 v2, s[64:65]
	v_mfma_f32_16x16x32_bf16 v[96:99], v[214:217], v[226:229], v[96:99]
	v_mfma_f32_16x16x32_bf16 v[36:39], v[218:221], v[226:229], v[36:39]
	ds_read_b128 v[226:229], v19
	s_waitcnt lgkmcnt(3)
	v_mfma_f32_16x16x32_bf16 v[104:107], v[158:161], v[162:165], v[104:107]
	s_waitcnt lgkmcnt(2)
	v_mfma_f32_16x16x32_bf16 v[116:119], v[158:161], v[178:181], v[116:119]
	s_waitcnt lgkmcnt(1)
	s_mov_b32 m0, s45
	v_mfma_f32_16x16x32_bf16 v[128:131], v[158:161], v[222:225], v[128:131]
	global_load_lds_dwordx4 v2, s[68:69]
	s_waitcnt lgkmcnt(0)
	v_mfma_f32_16x16x32_bf16 v[100:103], v[158:161], v[226:229], v[100:103]
	ds_read_b128 v[158:161], v20
	v_mfma_f32_16x16x32_bf16 v[108:111], v[166:169], v[162:165], v[108:111]
	v_mfma_f32_16x16x32_bf16 v[120:123], v[166:169], v[178:181], v[120:123]
	v_mfma_f32_16x16x32_bf16 v[132:135], v[166:169], v[222:225], v[132:135]
	s_mov_b32 m0, s46
	v_mfma_f32_16x16x32_bf16 v[140:143], v[166:169], v[226:229], v[140:143]
	global_load_lds_dwordx4 v4, s[64:65]
	ds_read_b128 v[166:169], v24
	v_mfma_f32_16x16x32_bf16 v[112:115], v[214:217], v[162:165], v[112:115]
	v_mfma_f32_16x16x32_bf16 v[52:55], v[218:221], v[162:165], v[52:55]
	ds_read_b128 v[162:165], v21
	v_mfma_f32_16x16x32_bf16 v[124:127], v[214:217], v[178:181], v[124:127]
	v_mfma_f32_16x16x32_bf16 v[68:71], v[218:221], v[178:181], v[68:71]
	ds_read_b128 v[178:181], v25
	s_mov_b32 m0, s47
	v_mfma_f32_16x16x32_bf16 v[136:139], v[214:217], v[222:225], v[136:139]
	global_load_lds_dwordx4 v4, s[68:69]
	v_mfma_f32_16x16x32_bf16 v[84:87], v[218:221], v[222:225], v[84:87]
	ds_read_b128 v[222:225], v26
	v_mfma_f32_16x16x32_bf16 v[150:153], v[214:217], v[226:229], v[150:153]
	ds_read_b128 v[214:217], v23
	v_mfma_f32_16x16x32_bf16 v[154:157], v[218:221], v[226:229], v[154:157]
	ds_read_b128 v[218:221], v22
	ds_read_b128 v[226:229], v27
	s_waitcnt lgkmcnt(6)
	v_mfma_f32_16x16x32_bf16 v[40:43], v[158:161], v[166:169], v[40:43]
	s_waitcnt lgkmcnt(5)
	s_mov_b32 m0, s49
	v_mfma_f32_16x16x32_bf16 v[44:47], v[162:165], v[166:169], v[44:47]
	global_load_lds_dwordx4 v146, s[64:65]
	s_waitcnt lgkmcnt(4)
	v_mfma_f32_16x16x32_bf16 v[56:59], v[158:161], v[178:181], v[56:59]
	v_mfma_f32_16x16x32_bf16 v[60:63], v[162:165], v[178:181], v[60:63]
	s_waitcnt lgkmcnt(3)
	v_mfma_f32_16x16x32_bf16 v[72:75], v[158:161], v[222:225], v[72:75]
	v_mfma_f32_16x16x32_bf16 v[76:79], v[162:165], v[222:225], v[76:79]
	s_waitcnt lgkmcnt(2)
	s_mov_b32 m0, s50
	v_mfma_f32_16x16x32_bf16 v[48:51], v[214:217], v[166:169], v[48:51]
	global_load_lds_dwordx4 v146, s[68:69]
	s_waitcnt lgkmcnt(1)
	v_mfma_f32_16x16x32_bf16 v[174:177], v[218:221], v[166:169], v[174:177]
	ds_read_b128 v[166:169], v28
	v_mfma_f32_16x16x32_bf16 v[64:67], v[214:217], v[178:181], v[64:67]
	v_mfma_f32_16x16x32_bf16 v[170:173], v[218:221], v[178:181], v[170:173]
	ds_read_b128 v[178:181], v29
	v_mfma_f32_16x16x32_bf16 v[80:83], v[214:217], v[222:225], v[80:83]
	v_mfma_f32_16x16x32_bf16 v[32:35], v[218:221], v[222:225], v[32:35]
	ds_read_b128 v[222:225], v30
	s_waitcnt lgkmcnt(3)
	v_mfma_f32_16x16x32_bf16 v[88:91], v[158:161], v[226:229], v[88:91]
	v_mfma_f32_16x16x32_bf16 v[92:95], v[162:165], v[226:229], v[92:95]
	v_mfma_f32_16x16x32_bf16 v[96:99], v[214:217], v[226:229], v[96:99]
	v_mfma_f32_16x16x32_bf16 v[36:39], v[218:221], v[226:229], v[36:39]
	ds_read_b128 v[226:229], v31
	s_waitcnt lgkmcnt(3)
	v_mfma_f32_16x16x32_bf16 v[104:107], v[158:161], v[166:169], v[104:107]
	v_mfma_f32_16x16x32_bf16 v[108:111], v[162:165], v[166:169], v[108:111]
	v_mfma_f32_16x16x32_bf16 v[112:115], v[214:217], v[166:169], v[112:115]
	v_mfma_f32_16x16x32_bf16 v[52:55], v[218:221], v[166:169], v[52:55]
	s_waitcnt lgkmcnt(2)
	v_mfma_f32_16x16x32_bf16 v[116:119], v[158:161], v[178:181], v[116:119]
	v_mfma_f32_16x16x32_bf16 v[120:123], v[162:165], v[178:181], v[120:123]
	v_mfma_f32_16x16x32_bf16 v[124:127], v[214:217], v[178:181], v[124:127]
	v_mfma_f32_16x16x32_bf16 v[68:71], v[218:221], v[178:181], v[68:71]
	s_waitcnt lgkmcnt(1)
	v_mfma_f32_16x16x32_bf16 v[128:131], v[158:161], v[222:225], v[128:131]
	v_mfma_f32_16x16x32_bf16 v[132:135], v[162:165], v[222:225], v[132:135]
	v_mfma_f32_16x16x32_bf16 v[136:139], v[214:217], v[222:225], v[136:139]
	v_mfma_f32_16x16x32_bf16 v[84:87], v[218:221], v[222:225], v[84:87]
	s_waitcnt lgkmcnt(0)
	v_mfma_f32_16x16x32_bf16 v[100:103], v[158:161], v[226:229], v[100:103]
	v_mfma_f32_16x16x32_bf16 v[140:143], v[162:165], v[226:229], v[140:143]
	v_mfma_f32_16x16x32_bf16 v[150:153], v[214:217], v[226:229], v[150:153]
	v_mfma_f32_16x16x32_bf16 v[154:157], v[218:221], v[226:229], v[154:157]
	s_add_u32 s64, s0, 0x480
	s_addc_u32 s65, s1, 0
	s_add_u32 s68, s14, 0x480
	s_waitcnt vmcnt(0)
	s_barrier
	s_addc_u32 s69, s15, 0
	ds_read_b128 v[158:161], v7 offset:32768
	ds_read_b128 v[162:165], v6
	ds_read_b128 v[166:169], v7 offset:34816
	ds_read_b128 v[178:181], v6 offset:2048
	ds_read_b128 v[214:217], v7 offset:36864
	ds_read_b128 v[218:221], v7 offset:38912
	ds_read_b128 v[222:225], v6 offset:4096
	ds_read_b128 v[226:229], v6 offset:6144
	s_waitcnt lgkmcnt(6)
	v_mfma_f32_16x16x32_bf16 v[40:43], v[158:161], v[162:165], v[40:43]
	s_waitcnt lgkmcnt(5)
	v_mfma_f32_16x16x32_bf16 v[44:47], v[166:169], v[162:165], v[44:47]
	s_waitcnt lgkmcnt(4)
	v_mfma_f32_16x16x32_bf16 v[56:59], v[158:161], v[178:181], v[56:59]
	s_mov_b32 m0, s52
	v_mfma_f32_16x16x32_bf16 v[60:63], v[166:169], v[178:181], v[60:63]
	global_load_lds_dwordx4 v0, s[64:65]
	s_waitcnt lgkmcnt(3)
	v_mfma_f32_16x16x32_bf16 v[48:51], v[214:217], v[162:165], v[48:51]
	v_mfma_f32_16x16x32_bf16 v[64:67], v[214:217], v[178:181], v[64:67]
	s_waitcnt lgkmcnt(2)
	v_mfma_f32_16x16x32_bf16 v[174:177], v[218:221], v[162:165], v[174:177]
	ds_read_b128 v[162:165], v6 offset:8192
	v_mfma_f32_16x16x32_bf16 v[170:173], v[218:221], v[178:181], v[170:173]
	ds_read_b128 v[178:181], v6 offset:10240
	s_waitcnt lgkmcnt(3)
	s_mov_b32 m0, s51
	v_mfma_f32_16x16x32_bf16 v[72:75], v[158:161], v[222:225], v[72:75]
	global_load_lds_dwordx4 v0, s[68:69]
	v_mfma_f32_16x16x32_bf16 v[76:79], v[166:169], v[222:225], v[76:79]
	v_mfma_f32_16x16x32_bf16 v[80:83], v[214:217], v[222:225], v[80:83]
	v_mfma_f32_16x16x32_bf16 v[32:35], v[218:221], v[222:225], v[32:35]
	ds_read_b128 v[222:225], v6 offset:12288
	s_waitcnt lgkmcnt(3)
	v_mfma_f32_16x16x32_bf16 v[88:91], v[158:161], v[226:229], v[88:91]
	s_mov_b32 m0, s53
	v_mfma_f32_16x16x32_bf16 v[92:95], v[166:169], v[226:229], v[92:95]
	global_load_lds_dwordx4 v2, s[64:65]
	v_mfma_f32_16x16x32_bf16 v[96:99], v[214:217], v[226:229], v[96:99]
	v_mfma_f32_16x16x32_bf16 v[36:39], v[218:221], v[226:229], v[36:39]
	ds_read_b128 v[226:229], v6 offset:14336
	s_waitcnt lgkmcnt(3)
	v_mfma_f32_16x16x32_bf16 v[104:107], v[158:161], v[162:165], v[104:107]
	s_waitcnt lgkmcnt(2)
	v_mfma_f32_16x16x32_bf16 v[116:119], v[158:161], v[178:181], v[116:119]
	s_waitcnt lgkmcnt(1)
	s_mov_b32 m0, s54
	v_mfma_f32_16x16x32_bf16 v[128:131], v[158:161], v[222:225], v[128:131]
	global_load_lds_dwordx4 v2, s[68:69]
	s_waitcnt lgkmcnt(0)
	v_mfma_f32_16x16x32_bf16 v[100:103], v[158:161], v[226:229], v[100:103]
	ds_read_b128 v[158:161], v7 offset:33792
	v_mfma_f32_16x16x32_bf16 v[108:111], v[166:169], v[162:165], v[108:111]
	v_mfma_f32_16x16x32_bf16 v[120:123], v[166:169], v[178:181], v[120:123]
	v_mfma_f32_16x16x32_bf16 v[132:135], v[166:169], v[222:225], v[132:135]
	s_mov_b32 m0, s55
	v_mfma_f32_16x16x32_bf16 v[140:143], v[166:169], v[226:229], v[140:143]
	global_load_lds_dwordx4 v4, s[64:65]
	ds_read_b128 v[166:169], v6 offset:1024
	v_mfma_f32_16x16x32_bf16 v[112:115], v[214:217], v[162:165], v[112:115]
	v_mfma_f32_16x16x32_bf16 v[52:55], v[218:221], v[162:165], v[52:55]
	ds_read_b128 v[162:165], v7 offset:35840
	v_mfma_f32_16x16x32_bf16 v[124:127], v[214:217], v[178:181], v[124:127]
	v_mfma_f32_16x16x32_bf16 v[68:71], v[218:221], v[178:181], v[68:71]
	ds_read_b128 v[178:181], v6 offset:3072
	s_mov_b32 m0, s58
	v_mfma_f32_16x16x32_bf16 v[136:139], v[214:217], v[222:225], v[136:139]
	global_load_lds_dwordx4 v4, s[68:69]
	v_mfma_f32_16x16x32_bf16 v[84:87], v[218:221], v[222:225], v[84:87]
	ds_read_b128 v[222:225], v6 offset:5120
	v_mfma_f32_16x16x32_bf16 v[150:153], v[214:217], v[226:229], v[150:153]
	ds_read_b128 v[214:217], v7 offset:37888
	v_mfma_f32_16x16x32_bf16 v[154:157], v[218:221], v[226:229], v[154:157]
	ds_read_b128 v[218:221], v7 offset:39936
	ds_read_b128 v[226:229], v6 offset:7168
	s_waitcnt lgkmcnt(6)
	v_mfma_f32_16x16x32_bf16 v[40:43], v[158:161], v[166:169], v[40:43]
	s_waitcnt lgkmcnt(5)
	s_mov_b32 m0, s62
	v_mfma_f32_16x16x32_bf16 v[44:47], v[162:165], v[166:169], v[44:47]
	global_load_lds_dwordx4 v146, s[64:65]
	s_waitcnt lgkmcnt(4)
	v_mfma_f32_16x16x32_bf16 v[56:59], v[158:161], v[178:181], v[56:59]
	v_mfma_f32_16x16x32_bf16 v[60:63], v[162:165], v[178:181], v[60:63]
	s_waitcnt lgkmcnt(3)
	v_mfma_f32_16x16x32_bf16 v[72:75], v[158:161], v[222:225], v[72:75]
	v_mfma_f32_16x16x32_bf16 v[76:79], v[162:165], v[222:225], v[76:79]
	s_waitcnt lgkmcnt(2)
	s_mov_b32 m0, s63
	v_mfma_f32_16x16x32_bf16 v[48:51], v[214:217], v[166:169], v[48:51]
	global_load_lds_dwordx4 v146, s[68:69]
	s_waitcnt lgkmcnt(1)
	v_mfma_f32_16x16x32_bf16 v[174:177], v[218:221], v[166:169], v[174:177]
	ds_read_b128 v[166:169], v6 offset:9216
	v_mfma_f32_16x16x32_bf16 v[64:67], v[214:217], v[178:181], v[64:67]
	v_mfma_f32_16x16x32_bf16 v[170:173], v[218:221], v[178:181], v[170:173]
	ds_read_b128 v[178:181], v6 offset:11264
	v_mfma_f32_16x16x32_bf16 v[80:83], v[214:217], v[222:225], v[80:83]
	v_mfma_f32_16x16x32_bf16 v[32:35], v[218:221], v[222:225], v[32:35]
	ds_read_b128 v[222:225], v6 offset:13312
	s_waitcnt lgkmcnt(3)
	v_mfma_f32_16x16x32_bf16 v[88:91], v[158:161], v[226:229], v[88:91]
	v_mfma_f32_16x16x32_bf16 v[92:95], v[162:165], v[226:229], v[92:95]
	v_mfma_f32_16x16x32_bf16 v[96:99], v[214:217], v[226:229], v[96:99]
	v_mfma_f32_16x16x32_bf16 v[36:39], v[218:221], v[226:229], v[36:39]
	ds_read_b128 v[226:229], v6 offset:15360
	s_waitcnt lgkmcnt(3)
	v_mfma_f32_16x16x32_bf16 v[104:107], v[158:161], v[166:169], v[104:107]
	v_mfma_f32_16x16x32_bf16 v[108:111], v[162:165], v[166:169], v[108:111]
	v_mfma_f32_16x16x32_bf16 v[112:115], v[214:217], v[166:169], v[112:115]
	v_mfma_f32_16x16x32_bf16 v[52:55], v[218:221], v[166:169], v[52:55]
	s_waitcnt lgkmcnt(2)
	v_mfma_f32_16x16x32_bf16 v[116:119], v[158:161], v[178:181], v[116:119]
	v_mfma_f32_16x16x32_bf16 v[120:123], v[162:165], v[178:181], v[120:123]
	v_mfma_f32_16x16x32_bf16 v[124:127], v[214:217], v[178:181], v[124:127]
	v_mfma_f32_16x16x32_bf16 v[68:71], v[218:221], v[178:181], v[68:71]
	s_waitcnt lgkmcnt(1)
	v_mfma_f32_16x16x32_bf16 v[128:131], v[158:161], v[222:225], v[128:131]
	v_mfma_f32_16x16x32_bf16 v[132:135], v[162:165], v[222:225], v[132:135]
	v_mfma_f32_16x16x32_bf16 v[136:139], v[214:217], v[222:225], v[136:139]
	v_mfma_f32_16x16x32_bf16 v[84:87], v[218:221], v[222:225], v[84:87]
	s_waitcnt lgkmcnt(0)
	v_mfma_f32_16x16x32_bf16 v[100:103], v[158:161], v[226:229], v[100:103]
	v_mfma_f32_16x16x32_bf16 v[140:143], v[162:165], v[226:229], v[140:143]
	v_mfma_f32_16x16x32_bf16 v[150:153], v[214:217], v[226:229], v[150:153]
	v_mfma_f32_16x16x32_bf16 v[154:157], v[218:221], v[226:229], v[154:157]
	s_add_u32 s64, s0, 0x500
	s_addc_u32 s65, s1, 0
	s_add_u32 s68, s14, 0x500
	s_waitcnt vmcnt(0)
	s_barrier
	s_addc_u32 s69, s15, 0
	ds_read_b128 v[158:161], v8
	ds_read_b128 v[162:165], v12
	ds_read_b128 v[166:169], v9
	ds_read_b128 v[178:181], v13
	ds_read_b128 v[214:217], v11
	ds_read_b128 v[218:221], v10
	ds_read_b128 v[222:225], v14
	ds_read_b128 v[226:229], v15
	s_waitcnt lgkmcnt(6)
	v_mfma_f32_16x16x32_bf16 v[40:43], v[158:161], v[162:165], v[40:43]
	s_waitcnt lgkmcnt(5)
	v_mfma_f32_16x16x32_bf16 v[44:47], v[166:169], v[162:165], v[44:47]
	s_waitcnt lgkmcnt(4)
	v_mfma_f32_16x16x32_bf16 v[56:59], v[158:161], v[178:181], v[56:59]
	s_mov_b32 m0, s42
	v_mfma_f32_16x16x32_bf16 v[60:63], v[166:169], v[178:181], v[60:63]
	global_load_lds_dwordx4 v0, s[64:65]
	s_waitcnt lgkmcnt(3)
	v_mfma_f32_16x16x32_bf16 v[48:51], v[214:217], v[162:165], v[48:51]
	v_mfma_f32_16x16x32_bf16 v[64:67], v[214:217], v[178:181], v[64:67]
	s_waitcnt lgkmcnt(2)
	v_mfma_f32_16x16x32_bf16 v[174:177], v[218:221], v[162:165], v[174:177]
	ds_read_b128 v[162:165], v16
	v_mfma_f32_16x16x32_bf16 v[170:173], v[218:221], v[178:181], v[170:173]
	ds_read_b128 v[178:181], v17
	s_waitcnt lgkmcnt(3)
	s_mov_b32 m0, s43
	v_mfma_f32_16x16x32_bf16 v[72:75], v[158:161], v[222:225], v[72:75]
	global_load_lds_dwordx4 v0, s[68:69]
	v_mfma_f32_16x16x32_bf16 v[76:79], v[166:169], v[222:225], v[76:79]
	v_mfma_f32_16x16x32_bf16 v[80:83], v[214:217], v[222:225], v[80:83]
	v_mfma_f32_16x16x32_bf16 v[32:35], v[218:221], v[222:225], v[32:35]
	ds_read_b128 v[222:225], v18
	s_waitcnt lgkmcnt(3)
	v_mfma_f32_16x16x32_bf16 v[88:91], v[158:161], v[226:229], v[88:91]
	s_mov_b32 m0, s44
	v_mfma_f32_16x16x32_bf16 v[92:95], v[166:169], v[226:229], v[92:95]
	global_load_lds_dwordx4 v2, s[64:65]
	v_mfma_f32_16x16x32_bf16 v[96:99], v[214:217], v[226:229], v[96:99]
	v_mfma_f32_16x16x32_bf16 v[36:39], v[218:221], v[226:229], v[36:39]
	ds_read_b128 v[226:229], v19
	s_waitcnt lgkmcnt(3)
	v_mfma_f32_16x16x32_bf16 v[104:107], v[158:161], v[162:165], v[104:107]
	s_waitcnt lgkmcnt(2)
	v_mfma_f32_16x16x32_bf16 v[116:119], v[158:161], v[178:181], v[116:119]
	s_waitcnt lgkmcnt(1)
	s_mov_b32 m0, s45
	v_mfma_f32_16x16x32_bf16 v[128:131], v[158:161], v[222:225], v[128:131]
	global_load_lds_dwordx4 v2, s[68:69]
	s_waitcnt lgkmcnt(0)
	v_mfma_f32_16x16x32_bf16 v[100:103], v[158:161], v[226:229], v[100:103]
	ds_read_b128 v[158:161], v20
	v_mfma_f32_16x16x32_bf16 v[108:111], v[166:169], v[162:165], v[108:111]
	v_mfma_f32_16x16x32_bf16 v[120:123], v[166:169], v[178:181], v[120:123]
	v_mfma_f32_16x16x32_bf16 v[132:135], v[166:169], v[222:225], v[132:135]
	s_mov_b32 m0, s46
	v_mfma_f32_16x16x32_bf16 v[140:143], v[166:169], v[226:229], v[140:143]
	global_load_lds_dwordx4 v4, s[64:65]
	ds_read_b128 v[166:169], v24
	v_mfma_f32_16x16x32_bf16 v[112:115], v[214:217], v[162:165], v[112:115]
	v_mfma_f32_16x16x32_bf16 v[52:55], v[218:221], v[162:165], v[52:55]
	ds_read_b128 v[162:165], v21
	v_mfma_f32_16x16x32_bf16 v[124:127], v[214:217], v[178:181], v[124:127]
	v_mfma_f32_16x16x32_bf16 v[68:71], v[218:221], v[178:181], v[68:71]
	ds_read_b128 v[178:181], v25
	s_mov_b32 m0, s47
	v_mfma_f32_16x16x32_bf16 v[136:139], v[214:217], v[222:225], v[136:139]
	global_load_lds_dwordx4 v4, s[68:69]
	v_mfma_f32_16x16x32_bf16 v[84:87], v[218:221], v[222:225], v[84:87]
	ds_read_b128 v[222:225], v26
	v_mfma_f32_16x16x32_bf16 v[150:153], v[214:217], v[226:229], v[150:153]
	ds_read_b128 v[214:217], v23
	v_mfma_f32_16x16x32_bf16 v[154:157], v[218:221], v[226:229], v[154:157]
	ds_read_b128 v[218:221], v22
	ds_read_b128 v[226:229], v27
	s_waitcnt lgkmcnt(6)
	v_mfma_f32_16x16x32_bf16 v[40:43], v[158:161], v[166:169], v[40:43]
	s_waitcnt lgkmcnt(5)
	s_mov_b32 m0, s49
	v_mfma_f32_16x16x32_bf16 v[44:47], v[162:165], v[166:169], v[44:47]
	global_load_lds_dwordx4 v146, s[64:65]
	s_waitcnt lgkmcnt(4)
	v_mfma_f32_16x16x32_bf16 v[56:59], v[158:161], v[178:181], v[56:59]
	v_mfma_f32_16x16x32_bf16 v[60:63], v[162:165], v[178:181], v[60:63]
	s_waitcnt lgkmcnt(3)
	v_mfma_f32_16x16x32_bf16 v[72:75], v[158:161], v[222:225], v[72:75]
	v_mfma_f32_16x16x32_bf16 v[76:79], v[162:165], v[222:225], v[76:79]
	s_waitcnt lgkmcnt(2)
	s_mov_b32 m0, s50
	v_mfma_f32_16x16x32_bf16 v[48:51], v[214:217], v[166:169], v[48:51]
	global_load_lds_dwordx4 v146, s[68:69]
	s_waitcnt lgkmcnt(1)
	v_mfma_f32_16x16x32_bf16 v[174:177], v[218:221], v[166:169], v[174:177]
	ds_read_b128 v[166:169], v28
	v_mfma_f32_16x16x32_bf16 v[64:67], v[214:217], v[178:181], v[64:67]
	v_mfma_f32_16x16x32_bf16 v[170:173], v[218:221], v[178:181], v[170:173]
	ds_read_b128 v[178:181], v29
	v_mfma_f32_16x16x32_bf16 v[80:83], v[214:217], v[222:225], v[80:83]
	v_mfma_f32_16x16x32_bf16 v[32:35], v[218:221], v[222:225], v[32:35]
	ds_read_b128 v[222:225], v30
	s_waitcnt lgkmcnt(3)
	v_mfma_f32_16x16x32_bf16 v[88:91], v[158:161], v[226:229], v[88:91]
	v_mfma_f32_16x16x32_bf16 v[92:95], v[162:165], v[226:229], v[92:95]
	v_mfma_f32_16x16x32_bf16 v[96:99], v[214:217], v[226:229], v[96:99]
	v_mfma_f32_16x16x32_bf16 v[36:39], v[218:221], v[226:229], v[36:39]
	ds_read_b128 v[226:229], v31
	s_waitcnt lgkmcnt(3)
	v_mfma_f32_16x16x32_bf16 v[104:107], v[158:161], v[166:169], v[104:107]
	v_mfma_f32_16x16x32_bf16 v[108:111], v[162:165], v[166:169], v[108:111]
	v_mfma_f32_16x16x32_bf16 v[112:115], v[214:217], v[166:169], v[112:115]
	v_mfma_f32_16x16x32_bf16 v[52:55], v[218:221], v[166:169], v[52:55]
	s_waitcnt lgkmcnt(2)
	v_mfma_f32_16x16x32_bf16 v[116:119], v[158:161], v[178:181], v[116:119]
	v_mfma_f32_16x16x32_bf16 v[120:123], v[162:165], v[178:181], v[120:123]
	v_mfma_f32_16x16x32_bf16 v[124:127], v[214:217], v[178:181], v[124:127]
	v_mfma_f32_16x16x32_bf16 v[68:71], v[218:221], v[178:181], v[68:71]
	s_waitcnt lgkmcnt(1)
	v_mfma_f32_16x16x32_bf16 v[128:131], v[158:161], v[222:225], v[128:131]
	v_mfma_f32_16x16x32_bf16 v[132:135], v[162:165], v[222:225], v[132:135]
	v_mfma_f32_16x16x32_bf16 v[136:139], v[214:217], v[222:225], v[136:139]
	v_mfma_f32_16x16x32_bf16 v[84:87], v[218:221], v[222:225], v[84:87]
	s_waitcnt lgkmcnt(0)
	v_mfma_f32_16x16x32_bf16 v[100:103], v[158:161], v[226:229], v[100:103]
	v_mfma_f32_16x16x32_bf16 v[140:143], v[162:165], v[226:229], v[140:143]
	v_mfma_f32_16x16x32_bf16 v[150:153], v[214:217], v[226:229], v[150:153]
	v_mfma_f32_16x16x32_bf16 v[154:157], v[218:221], v[226:229], v[154:157]
	s_add_u32 s64, s0, 0x580
	s_addc_u32 s65, s1, 0
	s_add_u32 s68, s14, 0x580
	s_waitcnt vmcnt(0)
	s_barrier
	s_addc_u32 s69, s15, 0
	ds_read_b128 v[158:161], v7 offset:32768
	ds_read_b128 v[162:165], v6
	ds_read_b128 v[166:169], v7 offset:34816
	ds_read_b128 v[178:181], v6 offset:2048
	ds_read_b128 v[214:217], v7 offset:36864
	ds_read_b128 v[218:221], v7 offset:38912
	ds_read_b128 v[222:225], v6 offset:4096
	ds_read_b128 v[226:229], v6 offset:6144
	s_waitcnt lgkmcnt(6)
	v_mfma_f32_16x16x32_bf16 v[40:43], v[158:161], v[162:165], v[40:43]
	s_waitcnt lgkmcnt(5)
	v_mfma_f32_16x16x32_bf16 v[44:47], v[166:169], v[162:165], v[44:47]
	s_waitcnt lgkmcnt(4)
	v_mfma_f32_16x16x32_bf16 v[56:59], v[158:161], v[178:181], v[56:59]
	s_mov_b32 m0, s52
	v_mfma_f32_16x16x32_bf16 v[60:63], v[166:169], v[178:181], v[60:63]
	global_load_lds_dwordx4 v0, s[64:65]
	s_waitcnt lgkmcnt(3)
	v_mfma_f32_16x16x32_bf16 v[48:51], v[214:217], v[162:165], v[48:51]
	v_mfma_f32_16x16x32_bf16 v[64:67], v[214:217], v[178:181], v[64:67]
	s_waitcnt lgkmcnt(2)
	v_mfma_f32_16x16x32_bf16 v[174:177], v[218:221], v[162:165], v[174:177]
	ds_read_b128 v[162:165], v6 offset:8192
	v_mfma_f32_16x16x32_bf16 v[170:173], v[218:221], v[178:181], v[170:173]
	ds_read_b128 v[178:181], v6 offset:10240
	s_waitcnt lgkmcnt(3)
	s_mov_b32 m0, s51
	v_mfma_f32_16x16x32_bf16 v[72:75], v[158:161], v[222:225], v[72:75]
	global_load_lds_dwordx4 v0, s[68:69]
	v_mfma_f32_16x16x32_bf16 v[76:79], v[166:169], v[222:225], v[76:79]
	v_mfma_f32_16x16x32_bf16 v[80:83], v[214:217], v[222:225], v[80:83]
	v_mfma_f32_16x16x32_bf16 v[32:35], v[218:221], v[222:225], v[32:35]
	ds_read_b128 v[222:225], v6 offset:12288
	s_waitcnt lgkmcnt(3)
	v_mfma_f32_16x16x32_bf16 v[88:91], v[158:161], v[226:229], v[88:91]
	s_mov_b32 m0, s53
	v_mfma_f32_16x16x32_bf16 v[92:95], v[166:169], v[226:229], v[92:95]
	global_load_lds_dwordx4 v2, s[64:65]
	v_mfma_f32_16x16x32_bf16 v[96:99], v[214:217], v[226:229], v[96:99]
	v_mfma_f32_16x16x32_bf16 v[36:39], v[218:221], v[226:229], v[36:39]
	ds_read_b128 v[226:229], v6 offset:14336
	s_waitcnt lgkmcnt(3)
	v_mfma_f32_16x16x32_bf16 v[104:107], v[158:161], v[162:165], v[104:107]
	s_waitcnt lgkmcnt(2)
	v_mfma_f32_16x16x32_bf16 v[116:119], v[158:161], v[178:181], v[116:119]
	s_waitcnt lgkmcnt(1)
	s_mov_b32 m0, s54
	v_mfma_f32_16x16x32_bf16 v[128:131], v[158:161], v[222:225], v[128:131]
	global_load_lds_dwordx4 v2, s[68:69]
	s_waitcnt lgkmcnt(0)
	v_mfma_f32_16x16x32_bf16 v[100:103], v[158:161], v[226:229], v[100:103]
	ds_read_b128 v[158:161], v7 offset:33792
	v_mfma_f32_16x16x32_bf16 v[108:111], v[166:169], v[162:165], v[108:111]
	v_mfma_f32_16x16x32_bf16 v[120:123], v[166:169], v[178:181], v[120:123]
	v_mfma_f32_16x16x32_bf16 v[132:135], v[166:169], v[222:225], v[132:135]
	s_mov_b32 m0, s55
	v_mfma_f32_16x16x32_bf16 v[140:143], v[166:169], v[226:229], v[140:143]
	global_load_lds_dwordx4 v4, s[64:65]
	ds_read_b128 v[166:169], v6 offset:1024
	v_mfma_f32_16x16x32_bf16 v[112:115], v[214:217], v[162:165], v[112:115]
	v_mfma_f32_16x16x32_bf16 v[52:55], v[218:221], v[162:165], v[52:55]
	ds_read_b128 v[162:165], v7 offset:35840
	v_mfma_f32_16x16x32_bf16 v[124:127], v[214:217], v[178:181], v[124:127]
	v_mfma_f32_16x16x32_bf16 v[68:71], v[218:221], v[178:181], v[68:71]
	ds_read_b128 v[178:181], v6 offset:3072
	s_mov_b32 m0, s58
	v_mfma_f32_16x16x32_bf16 v[136:139], v[214:217], v[222:225], v[136:139]
	global_load_lds_dwordx4 v4, s[68:69]
	v_mfma_f32_16x16x32_bf16 v[84:87], v[218:221], v[222:225], v[84:87]
	ds_read_b128 v[222:225], v6 offset:5120
	v_mfma_f32_16x16x32_bf16 v[150:153], v[214:217], v[226:229], v[150:153]
	ds_read_b128 v[214:217], v7 offset:37888
	v_mfma_f32_16x16x32_bf16 v[154:157], v[218:221], v[226:229], v[154:157]
	ds_read_b128 v[218:221], v7 offset:39936
	ds_read_b128 v[226:229], v6 offset:7168
	s_waitcnt lgkmcnt(6)
	v_mfma_f32_16x16x32_bf16 v[40:43], v[158:161], v[166:169], v[40:43]
	s_waitcnt lgkmcnt(5)
	s_mov_b32 m0, s62
	v_mfma_f32_16x16x32_bf16 v[44:47], v[162:165], v[166:169], v[44:47]
	global_load_lds_dwordx4 v146, s[64:65]
	s_waitcnt lgkmcnt(4)
	v_mfma_f32_16x16x32_bf16 v[56:59], v[158:161], v[178:181], v[56:59]
	v_mfma_f32_16x16x32_bf16 v[60:63], v[162:165], v[178:181], v[60:63]
	s_waitcnt lgkmcnt(3)
	v_mfma_f32_16x16x32_bf16 v[72:75], v[158:161], v[222:225], v[72:75]
	v_mfma_f32_16x16x32_bf16 v[76:79], v[162:165], v[222:225], v[76:79]
	s_waitcnt lgkmcnt(2)
	s_mov_b32 m0, s63
	v_mfma_f32_16x16x32_bf16 v[48:51], v[214:217], v[166:169], v[48:51]
	global_load_lds_dwordx4 v146, s[68:69]
	s_waitcnt lgkmcnt(1)
	v_mfma_f32_16x16x32_bf16 v[174:177], v[218:221], v[166:169], v[174:177]
	ds_read_b128 v[166:169], v6 offset:9216
	v_mfma_f32_16x16x32_bf16 v[64:67], v[214:217], v[178:181], v[64:67]
	v_mfma_f32_16x16x32_bf16 v[170:173], v[218:221], v[178:181], v[170:173]
	ds_read_b128 v[178:181], v6 offset:11264
	v_mfma_f32_16x16x32_bf16 v[80:83], v[214:217], v[222:225], v[80:83]
	v_mfma_f32_16x16x32_bf16 v[32:35], v[218:221], v[222:225], v[32:35]
	ds_read_b128 v[222:225], v6 offset:13312
	s_waitcnt lgkmcnt(3)
	v_mfma_f32_16x16x32_bf16 v[88:91], v[158:161], v[226:229], v[88:91]
	v_mfma_f32_16x16x32_bf16 v[92:95], v[162:165], v[226:229], v[92:95]
	v_mfma_f32_16x16x32_bf16 v[96:99], v[214:217], v[226:229], v[96:99]
	v_mfma_f32_16x16x32_bf16 v[36:39], v[218:221], v[226:229], v[36:39]
	ds_read_b128 v[226:229], v6 offset:15360
	s_waitcnt lgkmcnt(3)
	v_mfma_f32_16x16x32_bf16 v[104:107], v[158:161], v[166:169], v[104:107]
	v_mfma_f32_16x16x32_bf16 v[108:111], v[162:165], v[166:169], v[108:111]
	v_mfma_f32_16x16x32_bf16 v[112:115], v[214:217], v[166:169], v[112:115]
	v_mfma_f32_16x16x32_bf16 v[52:55], v[218:221], v[166:169], v[52:55]
	s_waitcnt lgkmcnt(2)
	v_mfma_f32_16x16x32_bf16 v[116:119], v[158:161], v[178:181], v[116:119]
	v_mfma_f32_16x16x32_bf16 v[120:123], v[162:165], v[178:181], v[120:123]
	v_mfma_f32_16x16x32_bf16 v[124:127], v[214:217], v[178:181], v[124:127]
	v_mfma_f32_16x16x32_bf16 v[68:71], v[218:221], v[178:181], v[68:71]
	s_waitcnt lgkmcnt(1)
	v_mfma_f32_16x16x32_bf16 v[128:131], v[158:161], v[222:225], v[128:131]
	v_mfma_f32_16x16x32_bf16 v[132:135], v[162:165], v[222:225], v[132:135]
	v_mfma_f32_16x16x32_bf16 v[136:139], v[214:217], v[222:225], v[136:139]
	v_mfma_f32_16x16x32_bf16 v[84:87], v[218:221], v[222:225], v[84:87]
	s_waitcnt lgkmcnt(0)
	v_mfma_f32_16x16x32_bf16 v[100:103], v[158:161], v[226:229], v[100:103]
	v_mfma_f32_16x16x32_bf16 v[140:143], v[162:165], v[226:229], v[140:143]
	v_mfma_f32_16x16x32_bf16 v[150:153], v[214:217], v[226:229], v[150:153]
	v_mfma_f32_16x16x32_bf16 v[154:157], v[218:221], v[226:229], v[154:157]
	s_add_u32 s64, s0, 0x600
	s_addc_u32 s65, s1, 0
	s_add_u32 s68, s14, 0x600
	s_waitcnt vmcnt(0)
	s_barrier
	s_addc_u32 s69, s15, 0
	ds_read_b128 v[158:161], v8
	ds_read_b128 v[162:165], v12
	ds_read_b128 v[166:169], v9
	ds_read_b128 v[178:181], v13
	ds_read_b128 v[214:217], v11
	ds_read_b128 v[218:221], v10
	ds_read_b128 v[222:225], v14
	ds_read_b128 v[226:229], v15
	s_waitcnt lgkmcnt(6)
	v_mfma_f32_16x16x32_bf16 v[40:43], v[158:161], v[162:165], v[40:43]
	s_waitcnt lgkmcnt(5)
	v_mfma_f32_16x16x32_bf16 v[44:47], v[166:169], v[162:165], v[44:47]
	s_waitcnt lgkmcnt(4)
	v_mfma_f32_16x16x32_bf16 v[56:59], v[158:161], v[178:181], v[56:59]
	s_mov_b32 m0, s42
	v_mfma_f32_16x16x32_bf16 v[60:63], v[166:169], v[178:181], v[60:63]
	global_load_lds_dwordx4 v0, s[64:65]
	s_waitcnt lgkmcnt(3)
	v_mfma_f32_16x16x32_bf16 v[48:51], v[214:217], v[162:165], v[48:51]
	v_mfma_f32_16x16x32_bf16 v[64:67], v[214:217], v[178:181], v[64:67]
	s_waitcnt lgkmcnt(2)
	v_mfma_f32_16x16x32_bf16 v[174:177], v[218:221], v[162:165], v[174:177]
	ds_read_b128 v[162:165], v16
	v_mfma_f32_16x16x32_bf16 v[170:173], v[218:221], v[178:181], v[170:173]
	ds_read_b128 v[178:181], v17
	s_waitcnt lgkmcnt(3)
	s_mov_b32 m0, s43
	v_mfma_f32_16x16x32_bf16 v[72:75], v[158:161], v[222:225], v[72:75]
	global_load_lds_dwordx4 v0, s[68:69]
	v_mfma_f32_16x16x32_bf16 v[76:79], v[166:169], v[222:225], v[76:79]
	v_mfma_f32_16x16x32_bf16 v[80:83], v[214:217], v[222:225], v[80:83]
	v_mfma_f32_16x16x32_bf16 v[32:35], v[218:221], v[222:225], v[32:35]
	ds_read_b128 v[222:225], v18
	s_waitcnt lgkmcnt(3)
	v_mfma_f32_16x16x32_bf16 v[88:91], v[158:161], v[226:229], v[88:91]
	s_mov_b32 m0, s44
	v_mfma_f32_16x16x32_bf16 v[92:95], v[166:169], v[226:229], v[92:95]
	global_load_lds_dwordx4 v2, s[64:65]
	v_mfma_f32_16x16x32_bf16 v[96:99], v[214:217], v[226:229], v[96:99]
	v_mfma_f32_16x16x32_bf16 v[36:39], v[218:221], v[226:229], v[36:39]
	ds_read_b128 v[226:229], v19
	s_waitcnt lgkmcnt(3)
	v_mfma_f32_16x16x32_bf16 v[104:107], v[158:161], v[162:165], v[104:107]
	s_waitcnt lgkmcnt(2)
	v_mfma_f32_16x16x32_bf16 v[116:119], v[158:161], v[178:181], v[116:119]
	s_waitcnt lgkmcnt(1)
	s_mov_b32 m0, s45
	v_mfma_f32_16x16x32_bf16 v[128:131], v[158:161], v[222:225], v[128:131]
	global_load_lds_dwordx4 v2, s[68:69]
	s_waitcnt lgkmcnt(0)
	v_mfma_f32_16x16x32_bf16 v[100:103], v[158:161], v[226:229], v[100:103]
	ds_read_b128 v[158:161], v20
	v_mfma_f32_16x16x32_bf16 v[108:111], v[166:169], v[162:165], v[108:111]
	v_mfma_f32_16x16x32_bf16 v[120:123], v[166:169], v[178:181], v[120:123]
	v_mfma_f32_16x16x32_bf16 v[132:135], v[166:169], v[222:225], v[132:135]
	s_mov_b32 m0, s46
	v_mfma_f32_16x16x32_bf16 v[140:143], v[166:169], v[226:229], v[140:143]
	global_load_lds_dwordx4 v4, s[64:65]
	ds_read_b128 v[166:169], v24
	v_mfma_f32_16x16x32_bf16 v[112:115], v[214:217], v[162:165], v[112:115]
	v_mfma_f32_16x16x32_bf16 v[52:55], v[218:221], v[162:165], v[52:55]
	ds_read_b128 v[162:165], v21
	v_mfma_f32_16x16x32_bf16 v[124:127], v[214:217], v[178:181], v[124:127]
	v_mfma_f32_16x16x32_bf16 v[68:71], v[218:221], v[178:181], v[68:71]
	ds_read_b128 v[178:181], v25
	s_mov_b32 m0, s47
	v_mfma_f32_16x16x32_bf16 v[136:139], v[214:217], v[222:225], v[136:139]
	global_load_lds_dwordx4 v4, s[68:69]
	v_mfma_f32_16x16x32_bf16 v[84:87], v[218:221], v[222:225], v[84:87]
	ds_read_b128 v[222:225], v26
	v_mfma_f32_16x16x32_bf16 v[150:153], v[214:217], v[226:229], v[150:153]
	ds_read_b128 v[214:217], v23
	v_mfma_f32_16x16x32_bf16 v[154:157], v[218:221], v[226:229], v[154:157]
	ds_read_b128 v[218:221], v22
	ds_read_b128 v[226:229], v27
	s_waitcnt lgkmcnt(6)
	v_mfma_f32_16x16x32_bf16 v[40:43], v[158:161], v[166:169], v[40:43]
	s_waitcnt lgkmcnt(5)
	s_mov_b32 m0, s49
	v_mfma_f32_16x16x32_bf16 v[44:47], v[162:165], v[166:169], v[44:47]
	global_load_lds_dwordx4 v146, s[64:65]
	s_waitcnt lgkmcnt(4)
	v_mfma_f32_16x16x32_bf16 v[56:59], v[158:161], v[178:181], v[56:59]
	v_mfma_f32_16x16x32_bf16 v[60:63], v[162:165], v[178:181], v[60:63]
	s_waitcnt lgkmcnt(3)
	v_mfma_f32_16x16x32_bf16 v[72:75], v[158:161], v[222:225], v[72:75]
	v_mfma_f32_16x16x32_bf16 v[76:79], v[162:165], v[222:225], v[76:79]
	s_waitcnt lgkmcnt(2)
	s_mov_b32 m0, s50
	v_mfma_f32_16x16x32_bf16 v[48:51], v[214:217], v[166:169], v[48:51]
	global_load_lds_dwordx4 v146, s[68:69]
	s_waitcnt lgkmcnt(1)
	v_mfma_f32_16x16x32_bf16 v[174:177], v[218:221], v[166:169], v[174:177]
	ds_read_b128 v[166:169], v28
	v_mfma_f32_16x16x32_bf16 v[64:67], v[214:217], v[178:181], v[64:67]
	v_mfma_f32_16x16x32_bf16 v[170:173], v[218:221], v[178:181], v[170:173]
	ds_read_b128 v[178:181], v29
	v_mfma_f32_16x16x32_bf16 v[80:83], v[214:217], v[222:225], v[80:83]
	v_mfma_f32_16x16x32_bf16 v[32:35], v[218:221], v[222:225], v[32:35]
	ds_read_b128 v[222:225], v30
	s_waitcnt lgkmcnt(3)
	v_mfma_f32_16x16x32_bf16 v[88:91], v[158:161], v[226:229], v[88:91]
	v_mfma_f32_16x16x32_bf16 v[92:95], v[162:165], v[226:229], v[92:95]
	v_mfma_f32_16x16x32_bf16 v[96:99], v[214:217], v[226:229], v[96:99]
	v_mfma_f32_16x16x32_bf16 v[36:39], v[218:221], v[226:229], v[36:39]
	ds_read_b128 v[226:229], v31
	s_waitcnt lgkmcnt(3)
	v_mfma_f32_16x16x32_bf16 v[104:107], v[158:161], v[166:169], v[104:107]
	v_mfma_f32_16x16x32_bf16 v[108:111], v[162:165], v[166:169], v[108:111]
	v_mfma_f32_16x16x32_bf16 v[112:115], v[214:217], v[166:169], v[112:115]
	v_mfma_f32_16x16x32_bf16 v[52:55], v[218:221], v[166:169], v[52:55]
	s_waitcnt lgkmcnt(2)
	v_mfma_f32_16x16x32_bf16 v[116:119], v[158:161], v[178:181], v[116:119]
	v_mfma_f32_16x16x32_bf16 v[120:123], v[162:165], v[178:181], v[120:123]
	v_mfma_f32_16x16x32_bf16 v[124:127], v[214:217], v[178:181], v[124:127]
	v_mfma_f32_16x16x32_bf16 v[68:71], v[218:221], v[178:181], v[68:71]
	s_waitcnt lgkmcnt(1)
	v_mfma_f32_16x16x32_bf16 v[128:131], v[158:161], v[222:225], v[128:131]
	v_mfma_f32_16x16x32_bf16 v[132:135], v[162:165], v[222:225], v[132:135]
	v_mfma_f32_16x16x32_bf16 v[136:139], v[214:217], v[222:225], v[136:139]
	v_mfma_f32_16x16x32_bf16 v[84:87], v[218:221], v[222:225], v[84:87]
	s_waitcnt lgkmcnt(0)
	v_mfma_f32_16x16x32_bf16 v[100:103], v[158:161], v[226:229], v[100:103]
	v_mfma_f32_16x16x32_bf16 v[140:143], v[162:165], v[226:229], v[140:143]
	v_mfma_f32_16x16x32_bf16 v[150:153], v[214:217], v[226:229], v[150:153]
	v_mfma_f32_16x16x32_bf16 v[154:157], v[218:221], v[226:229], v[154:157]
	s_add_u32 s64, s0, 0x680
	s_addc_u32 s65, s1, 0
	s_add_u32 s68, s14, 0x680
	s_waitcnt vmcnt(0)
	s_barrier
	s_addc_u32 s69, s15, 0
	ds_read_b128 v[158:161], v7 offset:32768
	ds_read_b128 v[162:165], v6
	ds_read_b128 v[166:169], v7 offset:34816
	ds_read_b128 v[178:181], v6 offset:2048
	ds_read_b128 v[214:217], v7 offset:36864
	ds_read_b128 v[218:221], v7 offset:38912
	ds_read_b128 v[222:225], v6 offset:4096
	ds_read_b128 v[226:229], v6 offset:6144
	s_waitcnt lgkmcnt(6)
	v_mfma_f32_16x16x32_bf16 v[40:43], v[158:161], v[162:165], v[40:43]
	s_waitcnt lgkmcnt(5)
	v_mfma_f32_16x16x32_bf16 v[44:47], v[166:169], v[162:165], v[44:47]
	s_waitcnt lgkmcnt(4)
	v_mfma_f32_16x16x32_bf16 v[56:59], v[158:161], v[178:181], v[56:59]
	s_mov_b32 m0, s52
	v_mfma_f32_16x16x32_bf16 v[60:63], v[166:169], v[178:181], v[60:63]
	global_load_lds_dwordx4 v0, s[64:65]
	s_waitcnt lgkmcnt(3)
	v_mfma_f32_16x16x32_bf16 v[48:51], v[214:217], v[162:165], v[48:51]
	v_mfma_f32_16x16x32_bf16 v[64:67], v[214:217], v[178:181], v[64:67]
	s_waitcnt lgkmcnt(2)
	v_mfma_f32_16x16x32_bf16 v[174:177], v[218:221], v[162:165], v[174:177]
	ds_read_b128 v[162:165], v6 offset:8192
	v_mfma_f32_16x16x32_bf16 v[170:173], v[218:221], v[178:181], v[170:173]
	ds_read_b128 v[178:181], v6 offset:10240
	s_waitcnt lgkmcnt(3)
	s_mov_b32 m0, s51
	v_mfma_f32_16x16x32_bf16 v[72:75], v[158:161], v[222:225], v[72:75]
	global_load_lds_dwordx4 v0, s[68:69]
	v_mfma_f32_16x16x32_bf16 v[76:79], v[166:169], v[222:225], v[76:79]
	v_mfma_f32_16x16x32_bf16 v[80:83], v[214:217], v[222:225], v[80:83]
	v_mfma_f32_16x16x32_bf16 v[32:35], v[218:221], v[222:225], v[32:35]
	ds_read_b128 v[222:225], v6 offset:12288
	s_waitcnt lgkmcnt(3)
	v_mfma_f32_16x16x32_bf16 v[88:91], v[158:161], v[226:229], v[88:91]
	s_mov_b32 m0, s53
	v_mfma_f32_16x16x32_bf16 v[92:95], v[166:169], v[226:229], v[92:95]
	global_load_lds_dwordx4 v2, s[64:65]
	v_mfma_f32_16x16x32_bf16 v[96:99], v[214:217], v[226:229], v[96:99]
	v_mfma_f32_16x16x32_bf16 v[36:39], v[218:221], v[226:229], v[36:39]
	ds_read_b128 v[226:229], v6 offset:14336
	s_waitcnt lgkmcnt(3)
	v_mfma_f32_16x16x32_bf16 v[104:107], v[158:161], v[162:165], v[104:107]
	s_waitcnt lgkmcnt(2)
	v_mfma_f32_16x16x32_bf16 v[116:119], v[158:161], v[178:181], v[116:119]
	s_waitcnt lgkmcnt(1)
	s_mov_b32 m0, s54
	v_mfma_f32_16x16x32_bf16 v[128:131], v[158:161], v[222:225], v[128:131]
	global_load_lds_dwordx4 v2, s[68:69]
	s_waitcnt lgkmcnt(0)
	v_mfma_f32_16x16x32_bf16 v[100:103], v[158:161], v[226:229], v[100:103]
	ds_read_b128 v[158:161], v7 offset:33792
	v_mfma_f32_16x16x32_bf16 v[108:111], v[166:169], v[162:165], v[108:111]
	v_mfma_f32_16x16x32_bf16 v[120:123], v[166:169], v[178:181], v[120:123]
	v_mfma_f32_16x16x32_bf16 v[132:135], v[166:169], v[222:225], v[132:135]
	s_mov_b32 m0, s55
	v_mfma_f32_16x16x32_bf16 v[140:143], v[166:169], v[226:229], v[140:143]
	global_load_lds_dwordx4 v4, s[64:65]
	ds_read_b128 v[166:169], v6 offset:1024
	v_mfma_f32_16x16x32_bf16 v[112:115], v[214:217], v[162:165], v[112:115]
	v_mfma_f32_16x16x32_bf16 v[52:55], v[218:221], v[162:165], v[52:55]
	ds_read_b128 v[162:165], v7 offset:35840
	v_mfma_f32_16x16x32_bf16 v[124:127], v[214:217], v[178:181], v[124:127]
	v_mfma_f32_16x16x32_bf16 v[68:71], v[218:221], v[178:181], v[68:71]
	ds_read_b128 v[178:181], v6 offset:3072
	s_mov_b32 m0, s58
	v_mfma_f32_16x16x32_bf16 v[136:139], v[214:217], v[222:225], v[136:139]
	global_load_lds_dwordx4 v4, s[68:69]
	v_mfma_f32_16x16x32_bf16 v[84:87], v[218:221], v[222:225], v[84:87]
	ds_read_b128 v[222:225], v6 offset:5120
	v_mfma_f32_16x16x32_bf16 v[150:153], v[214:217], v[226:229], v[150:153]
	ds_read_b128 v[214:217], v7 offset:37888
	v_mfma_f32_16x16x32_bf16 v[154:157], v[218:221], v[226:229], v[154:157]
	ds_read_b128 v[218:221], v7 offset:39936
	ds_read_b128 v[226:229], v6 offset:7168
	s_waitcnt lgkmcnt(6)
	v_mfma_f32_16x16x32_bf16 v[40:43], v[158:161], v[166:169], v[40:43]
	s_waitcnt lgkmcnt(5)
	s_mov_b32 m0, s62
	v_mfma_f32_16x16x32_bf16 v[44:47], v[162:165], v[166:169], v[44:47]
	global_load_lds_dwordx4 v146, s[64:65]
	s_waitcnt lgkmcnt(4)
	v_mfma_f32_16x16x32_bf16 v[56:59], v[158:161], v[178:181], v[56:59]
	v_mfma_f32_16x16x32_bf16 v[60:63], v[162:165], v[178:181], v[60:63]
	s_waitcnt lgkmcnt(3)
	v_mfma_f32_16x16x32_bf16 v[72:75], v[158:161], v[222:225], v[72:75]
	v_mfma_f32_16x16x32_bf16 v[76:79], v[162:165], v[222:225], v[76:79]
	s_waitcnt lgkmcnt(2)
	s_mov_b32 m0, s63
	v_mfma_f32_16x16x32_bf16 v[48:51], v[214:217], v[166:169], v[48:51]
	global_load_lds_dwordx4 v146, s[68:69]
	s_waitcnt lgkmcnt(1)
	v_mfma_f32_16x16x32_bf16 v[174:177], v[218:221], v[166:169], v[174:177]
	ds_read_b128 v[166:169], v6 offset:9216
	v_mfma_f32_16x16x32_bf16 v[64:67], v[214:217], v[178:181], v[64:67]
	v_mfma_f32_16x16x32_bf16 v[170:173], v[218:221], v[178:181], v[170:173]
	ds_read_b128 v[178:181], v6 offset:11264
	v_mfma_f32_16x16x32_bf16 v[80:83], v[214:217], v[222:225], v[80:83]
	v_mfma_f32_16x16x32_bf16 v[32:35], v[218:221], v[222:225], v[32:35]
	ds_read_b128 v[222:225], v6 offset:13312
	s_waitcnt lgkmcnt(3)
	v_mfma_f32_16x16x32_bf16 v[88:91], v[158:161], v[226:229], v[88:91]
	v_mfma_f32_16x16x32_bf16 v[92:95], v[162:165], v[226:229], v[92:95]
	v_mfma_f32_16x16x32_bf16 v[96:99], v[214:217], v[226:229], v[96:99]
	v_mfma_f32_16x16x32_bf16 v[36:39], v[218:221], v[226:229], v[36:39]
	ds_read_b128 v[226:229], v6 offset:15360
	s_waitcnt lgkmcnt(3)
	v_mfma_f32_16x16x32_bf16 v[104:107], v[158:161], v[166:169], v[104:107]
	v_mfma_f32_16x16x32_bf16 v[108:111], v[162:165], v[166:169], v[108:111]
	v_mfma_f32_16x16x32_bf16 v[112:115], v[214:217], v[166:169], v[112:115]
	v_mfma_f32_16x16x32_bf16 v[52:55], v[218:221], v[166:169], v[52:55]
	s_waitcnt lgkmcnt(2)
	v_mfma_f32_16x16x32_bf16 v[116:119], v[158:161], v[178:181], v[116:119]
	v_mfma_f32_16x16x32_bf16 v[120:123], v[162:165], v[178:181], v[120:123]
	v_mfma_f32_16x16x32_bf16 v[124:127], v[214:217], v[178:181], v[124:127]
	v_mfma_f32_16x16x32_bf16 v[68:71], v[218:221], v[178:181], v[68:71]
	s_waitcnt lgkmcnt(1)
	v_mfma_f32_16x16x32_bf16 v[128:131], v[158:161], v[222:225], v[128:131]
	v_mfma_f32_16x16x32_bf16 v[132:135], v[162:165], v[222:225], v[132:135]
	v_mfma_f32_16x16x32_bf16 v[136:139], v[214:217], v[222:225], v[136:139]
	v_mfma_f32_16x16x32_bf16 v[84:87], v[218:221], v[222:225], v[84:87]
	s_waitcnt lgkmcnt(0)
	v_mfma_f32_16x16x32_bf16 v[100:103], v[158:161], v[226:229], v[100:103]
	v_mfma_f32_16x16x32_bf16 v[140:143], v[162:165], v[226:229], v[140:143]
	v_mfma_f32_16x16x32_bf16 v[150:153], v[214:217], v[226:229], v[150:153]
	v_mfma_f32_16x16x32_bf16 v[154:157], v[218:221], v[226:229], v[154:157]
	s_add_u32 s64, s0, 0x700
	s_addc_u32 s65, s1, 0
	s_add_u32 s68, s14, 0x700
	s_waitcnt vmcnt(0)
	s_barrier
	s_addc_u32 s69, s15, 0
	ds_read_b128 v[158:161], v8
	ds_read_b128 v[162:165], v12
	ds_read_b128 v[166:169], v9
	ds_read_b128 v[178:181], v13
	ds_read_b128 v[214:217], v11
	ds_read_b128 v[218:221], v10
	ds_read_b128 v[222:225], v14
	ds_read_b128 v[226:229], v15
	s_waitcnt lgkmcnt(6)
	v_mfma_f32_16x16x32_bf16 v[40:43], v[158:161], v[162:165], v[40:43]
	s_waitcnt lgkmcnt(5)
	v_mfma_f32_16x16x32_bf16 v[44:47], v[166:169], v[162:165], v[44:47]
	s_waitcnt lgkmcnt(4)
	v_mfma_f32_16x16x32_bf16 v[56:59], v[158:161], v[178:181], v[56:59]
	s_mov_b32 m0, s42
	v_mfma_f32_16x16x32_bf16 v[60:63], v[166:169], v[178:181], v[60:63]
	global_load_lds_dwordx4 v0, s[64:65]
	s_waitcnt lgkmcnt(3)
	v_mfma_f32_16x16x32_bf16 v[48:51], v[214:217], v[162:165], v[48:51]
	v_mfma_f32_16x16x32_bf16 v[64:67], v[214:217], v[178:181], v[64:67]
	s_waitcnt lgkmcnt(2)
	v_mfma_f32_16x16x32_bf16 v[174:177], v[218:221], v[162:165], v[174:177]
	ds_read_b128 v[162:165], v16
	v_mfma_f32_16x16x32_bf16 v[170:173], v[218:221], v[178:181], v[170:173]
	ds_read_b128 v[178:181], v17
	s_waitcnt lgkmcnt(3)
	s_mov_b32 m0, s43
	v_mfma_f32_16x16x32_bf16 v[72:75], v[158:161], v[222:225], v[72:75]
	global_load_lds_dwordx4 v0, s[68:69]
	v_mfma_f32_16x16x32_bf16 v[76:79], v[166:169], v[222:225], v[76:79]
	v_mfma_f32_16x16x32_bf16 v[80:83], v[214:217], v[222:225], v[80:83]
	v_mfma_f32_16x16x32_bf16 v[32:35], v[218:221], v[222:225], v[32:35]
	ds_read_b128 v[222:225], v18
	s_waitcnt lgkmcnt(3)
	v_mfma_f32_16x16x32_bf16 v[88:91], v[158:161], v[226:229], v[88:91]
	s_mov_b32 m0, s44
	v_mfma_f32_16x16x32_bf16 v[92:95], v[166:169], v[226:229], v[92:95]
	global_load_lds_dwordx4 v2, s[64:65]
	v_mfma_f32_16x16x32_bf16 v[96:99], v[214:217], v[226:229], v[96:99]
	v_mfma_f32_16x16x32_bf16 v[36:39], v[218:221], v[226:229], v[36:39]
	ds_read_b128 v[226:229], v19
	s_waitcnt lgkmcnt(3)
	v_mfma_f32_16x16x32_bf16 v[104:107], v[158:161], v[162:165], v[104:107]
	s_waitcnt lgkmcnt(2)
	v_mfma_f32_16x16x32_bf16 v[116:119], v[158:161], v[178:181], v[116:119]
	s_waitcnt lgkmcnt(1)
	s_mov_b32 m0, s45
	v_mfma_f32_16x16x32_bf16 v[128:131], v[158:161], v[222:225], v[128:131]
	global_load_lds_dwordx4 v2, s[68:69]
	s_waitcnt lgkmcnt(0)
	v_mfma_f32_16x16x32_bf16 v[100:103], v[158:161], v[226:229], v[100:103]
	ds_read_b128 v[158:161], v20
	v_mfma_f32_16x16x32_bf16 v[108:111], v[166:169], v[162:165], v[108:111]
	v_mfma_f32_16x16x32_bf16 v[120:123], v[166:169], v[178:181], v[120:123]
	v_mfma_f32_16x16x32_bf16 v[132:135], v[166:169], v[222:225], v[132:135]
	s_mov_b32 m0, s46
	v_mfma_f32_16x16x32_bf16 v[140:143], v[166:169], v[226:229], v[140:143]
	global_load_lds_dwordx4 v4, s[64:65]
	ds_read_b128 v[166:169], v24
	v_mfma_f32_16x16x32_bf16 v[112:115], v[214:217], v[162:165], v[112:115]
	v_mfma_f32_16x16x32_bf16 v[52:55], v[218:221], v[162:165], v[52:55]
	ds_read_b128 v[162:165], v21
	v_mfma_f32_16x16x32_bf16 v[124:127], v[214:217], v[178:181], v[124:127]
	v_mfma_f32_16x16x32_bf16 v[68:71], v[218:221], v[178:181], v[68:71]
	ds_read_b128 v[178:181], v25
	s_mov_b32 m0, s47
	v_mfma_f32_16x16x32_bf16 v[136:139], v[214:217], v[222:225], v[136:139]
	global_load_lds_dwordx4 v4, s[68:69]
	v_mfma_f32_16x16x32_bf16 v[84:87], v[218:221], v[222:225], v[84:87]
	ds_read_b128 v[222:225], v26
	v_mfma_f32_16x16x32_bf16 v[150:153], v[214:217], v[226:229], v[150:153]
	ds_read_b128 v[214:217], v23
	v_mfma_f32_16x16x32_bf16 v[154:157], v[218:221], v[226:229], v[154:157]
	ds_read_b128 v[218:221], v22
	ds_read_b128 v[226:229], v27
	s_waitcnt lgkmcnt(6)
	v_mfma_f32_16x16x32_bf16 v[40:43], v[158:161], v[166:169], v[40:43]
	s_waitcnt lgkmcnt(5)
	s_mov_b32 m0, s49
	v_mfma_f32_16x16x32_bf16 v[44:47], v[162:165], v[166:169], v[44:47]
	global_load_lds_dwordx4 v146, s[64:65]
	s_waitcnt lgkmcnt(4)
	v_mfma_f32_16x16x32_bf16 v[56:59], v[158:161], v[178:181], v[56:59]
	v_mfma_f32_16x16x32_bf16 v[60:63], v[162:165], v[178:181], v[60:63]
	s_waitcnt lgkmcnt(3)
	v_mfma_f32_16x16x32_bf16 v[72:75], v[158:161], v[222:225], v[72:75]
	v_mfma_f32_16x16x32_bf16 v[76:79], v[162:165], v[222:225], v[76:79]
	s_waitcnt lgkmcnt(2)
	s_mov_b32 m0, s50
	v_mfma_f32_16x16x32_bf16 v[48:51], v[214:217], v[166:169], v[48:51]
	global_load_lds_dwordx4 v146, s[68:69]
	s_waitcnt lgkmcnt(1)
	v_mfma_f32_16x16x32_bf16 v[174:177], v[218:221], v[166:169], v[174:177]
	ds_read_b128 v[166:169], v28
	v_mfma_f32_16x16x32_bf16 v[64:67], v[214:217], v[178:181], v[64:67]
	v_mfma_f32_16x16x32_bf16 v[170:173], v[218:221], v[178:181], v[170:173]
	ds_read_b128 v[178:181], v29
	v_mfma_f32_16x16x32_bf16 v[80:83], v[214:217], v[222:225], v[80:83]
	v_mfma_f32_16x16x32_bf16 v[32:35], v[218:221], v[222:225], v[32:35]
	ds_read_b128 v[222:225], v30
	s_waitcnt lgkmcnt(3)
	v_mfma_f32_16x16x32_bf16 v[88:91], v[158:161], v[226:229], v[88:91]
	v_mfma_f32_16x16x32_bf16 v[92:95], v[162:165], v[226:229], v[92:95]
	v_mfma_f32_16x16x32_bf16 v[96:99], v[214:217], v[226:229], v[96:99]
	v_mfma_f32_16x16x32_bf16 v[36:39], v[218:221], v[226:229], v[36:39]
	ds_read_b128 v[226:229], v31
	s_waitcnt lgkmcnt(3)
	v_mfma_f32_16x16x32_bf16 v[104:107], v[158:161], v[166:169], v[104:107]
	v_mfma_f32_16x16x32_bf16 v[108:111], v[162:165], v[166:169], v[108:111]
	v_mfma_f32_16x16x32_bf16 v[112:115], v[214:217], v[166:169], v[112:115]
	v_mfma_f32_16x16x32_bf16 v[52:55], v[218:221], v[166:169], v[52:55]
	s_waitcnt lgkmcnt(2)
	v_mfma_f32_16x16x32_bf16 v[116:119], v[158:161], v[178:181], v[116:119]
	v_mfma_f32_16x16x32_bf16 v[120:123], v[162:165], v[178:181], v[120:123]
	v_mfma_f32_16x16x32_bf16 v[124:127], v[214:217], v[178:181], v[124:127]
	v_mfma_f32_16x16x32_bf16 v[68:71], v[218:221], v[178:181], v[68:71]
	s_waitcnt lgkmcnt(1)
	v_mfma_f32_16x16x32_bf16 v[128:131], v[158:161], v[222:225], v[128:131]
	v_mfma_f32_16x16x32_bf16 v[132:135], v[162:165], v[222:225], v[132:135]
	v_mfma_f32_16x16x32_bf16 v[136:139], v[214:217], v[222:225], v[136:139]
	v_mfma_f32_16x16x32_bf16 v[84:87], v[218:221], v[222:225], v[84:87]
	s_waitcnt lgkmcnt(0)
	v_mfma_f32_16x16x32_bf16 v[100:103], v[158:161], v[226:229], v[100:103]
	v_mfma_f32_16x16x32_bf16 v[140:143], v[162:165], v[226:229], v[140:143]
	v_mfma_f32_16x16x32_bf16 v[150:153], v[214:217], v[226:229], v[150:153]
	v_mfma_f32_16x16x32_bf16 v[154:157], v[218:221], v[226:229], v[154:157]
	s_add_u32 s64, s0, 0x780
	s_addc_u32 s65, s1, 0
	s_add_u32 s68, s14, 0x780
	s_waitcnt vmcnt(0)
	s_barrier
	s_addc_u32 s69, s15, 0
	ds_read_b128 v[158:161], v7 offset:32768
	ds_read_b128 v[162:165], v6
	ds_read_b128 v[166:169], v7 offset:34816
	ds_read_b128 v[178:181], v6 offset:2048
	ds_read_b128 v[214:217], v7 offset:36864
	ds_read_b128 v[218:221], v7 offset:38912
	ds_read_b128 v[222:225], v6 offset:4096
	ds_read_b128 v[226:229], v6 offset:6144
	s_waitcnt lgkmcnt(6)
	v_mfma_f32_16x16x32_bf16 v[40:43], v[158:161], v[162:165], v[40:43]
	s_waitcnt lgkmcnt(5)
	v_mfma_f32_16x16x32_bf16 v[44:47], v[166:169], v[162:165], v[44:47]
	s_waitcnt lgkmcnt(4)
	v_mfma_f32_16x16x32_bf16 v[56:59], v[158:161], v[178:181], v[56:59]
	s_mov_b32 m0, s52
	v_mfma_f32_16x16x32_bf16 v[60:63], v[166:169], v[178:181], v[60:63]
	global_load_lds_dwordx4 v0, s[64:65]
	s_waitcnt lgkmcnt(3)
	v_mfma_f32_16x16x32_bf16 v[48:51], v[214:217], v[162:165], v[48:51]
	v_mfma_f32_16x16x32_bf16 v[64:67], v[214:217], v[178:181], v[64:67]
	s_waitcnt lgkmcnt(2)
	v_mfma_f32_16x16x32_bf16 v[174:177], v[218:221], v[162:165], v[174:177]
	ds_read_b128 v[162:165], v6 offset:8192
	v_mfma_f32_16x16x32_bf16 v[170:173], v[218:221], v[178:181], v[170:173]
	ds_read_b128 v[178:181], v6 offset:10240
	s_waitcnt lgkmcnt(3)
	s_mov_b32 m0, s51
	v_mfma_f32_16x16x32_bf16 v[72:75], v[158:161], v[222:225], v[72:75]
	global_load_lds_dwordx4 v0, s[68:69]
	v_mfma_f32_16x16x32_bf16 v[76:79], v[166:169], v[222:225], v[76:79]
	v_mfma_f32_16x16x32_bf16 v[80:83], v[214:217], v[222:225], v[80:83]
	v_mfma_f32_16x16x32_bf16 v[32:35], v[218:221], v[222:225], v[32:35]
	ds_read_b128 v[222:225], v6 offset:12288
	s_waitcnt lgkmcnt(3)
	v_mfma_f32_16x16x32_bf16 v[88:91], v[158:161], v[226:229], v[88:91]
	s_mov_b32 m0, s53
	v_mfma_f32_16x16x32_bf16 v[92:95], v[166:169], v[226:229], v[92:95]
	global_load_lds_dwordx4 v2, s[64:65]
	v_mfma_f32_16x16x32_bf16 v[96:99], v[214:217], v[226:229], v[96:99]
	v_mfma_f32_16x16x32_bf16 v[36:39], v[218:221], v[226:229], v[36:39]
	ds_read_b128 v[226:229], v6 offset:14336
	s_waitcnt lgkmcnt(3)
	v_mfma_f32_16x16x32_bf16 v[104:107], v[158:161], v[162:165], v[104:107]
	s_waitcnt lgkmcnt(2)
	v_mfma_f32_16x16x32_bf16 v[116:119], v[158:161], v[178:181], v[116:119]
	s_waitcnt lgkmcnt(1)
	s_mov_b32 m0, s54
	v_mfma_f32_16x16x32_bf16 v[128:131], v[158:161], v[222:225], v[128:131]
	global_load_lds_dwordx4 v2, s[68:69]
	s_waitcnt lgkmcnt(0)
	v_mfma_f32_16x16x32_bf16 v[100:103], v[158:161], v[226:229], v[100:103]
	ds_read_b128 v[158:161], v7 offset:33792
	v_mfma_f32_16x16x32_bf16 v[108:111], v[166:169], v[162:165], v[108:111]
	v_mfma_f32_16x16x32_bf16 v[120:123], v[166:169], v[178:181], v[120:123]
	v_mfma_f32_16x16x32_bf16 v[132:135], v[166:169], v[222:225], v[132:135]
	s_mov_b32 m0, s55
	v_mfma_f32_16x16x32_bf16 v[140:143], v[166:169], v[226:229], v[140:143]
	global_load_lds_dwordx4 v4, s[64:65]
	ds_read_b128 v[166:169], v6 offset:1024
	v_mfma_f32_16x16x32_bf16 v[112:115], v[214:217], v[162:165], v[112:115]
	v_mfma_f32_16x16x32_bf16 v[52:55], v[218:221], v[162:165], v[52:55]
	ds_read_b128 v[162:165], v7 offset:35840
	v_mfma_f32_16x16x32_bf16 v[124:127], v[214:217], v[178:181], v[124:127]
	v_mfma_f32_16x16x32_bf16 v[68:71], v[218:221], v[178:181], v[68:71]
	ds_read_b128 v[178:181], v6 offset:3072
	s_mov_b32 m0, s58
	v_mfma_f32_16x16x32_bf16 v[136:139], v[214:217], v[222:225], v[136:139]
	global_load_lds_dwordx4 v4, s[68:69]
	v_mfma_f32_16x16x32_bf16 v[84:87], v[218:221], v[222:225], v[84:87]
	ds_read_b128 v[222:225], v6 offset:5120
	v_mfma_f32_16x16x32_bf16 v[150:153], v[214:217], v[226:229], v[150:153]
	ds_read_b128 v[214:217], v7 offset:37888
	v_mfma_f32_16x16x32_bf16 v[154:157], v[218:221], v[226:229], v[154:157]
	ds_read_b128 v[218:221], v7 offset:39936
	ds_read_b128 v[226:229], v6 offset:7168
	s_waitcnt lgkmcnt(6)
	v_mfma_f32_16x16x32_bf16 v[40:43], v[158:161], v[166:169], v[40:43]
	s_waitcnt lgkmcnt(5)
	s_mov_b32 m0, s62
	v_mfma_f32_16x16x32_bf16 v[44:47], v[162:165], v[166:169], v[44:47]
	global_load_lds_dwordx4 v146, s[64:65]
	s_waitcnt lgkmcnt(4)
	v_mfma_f32_16x16x32_bf16 v[56:59], v[158:161], v[178:181], v[56:59]
	v_mfma_f32_16x16x32_bf16 v[60:63], v[162:165], v[178:181], v[60:63]
	s_waitcnt lgkmcnt(3)
	v_mfma_f32_16x16x32_bf16 v[72:75], v[158:161], v[222:225], v[72:75]
	v_mfma_f32_16x16x32_bf16 v[76:79], v[162:165], v[222:225], v[76:79]
	s_waitcnt lgkmcnt(2)
	s_mov_b32 m0, s63
	v_mfma_f32_16x16x32_bf16 v[48:51], v[214:217], v[166:169], v[48:51]
	global_load_lds_dwordx4 v146, s[68:69]
	s_waitcnt lgkmcnt(1)
	v_mfma_f32_16x16x32_bf16 v[174:177], v[218:221], v[166:169], v[174:177]
	ds_read_b128 v[166:169], v6 offset:9216
	v_mfma_f32_16x16x32_bf16 v[64:67], v[214:217], v[178:181], v[64:67]
	v_mfma_f32_16x16x32_bf16 v[170:173], v[218:221], v[178:181], v[170:173]
	ds_read_b128 v[178:181], v6 offset:11264
	v_mfma_f32_16x16x32_bf16 v[80:83], v[214:217], v[222:225], v[80:83]
	v_mfma_f32_16x16x32_bf16 v[32:35], v[218:221], v[222:225], v[32:35]
	ds_read_b128 v[222:225], v6 offset:13312
	s_waitcnt lgkmcnt(3)
	v_mfma_f32_16x16x32_bf16 v[88:91], v[158:161], v[226:229], v[88:91]
	v_mfma_f32_16x16x32_bf16 v[92:95], v[162:165], v[226:229], v[92:95]
	v_mfma_f32_16x16x32_bf16 v[96:99], v[214:217], v[226:229], v[96:99]
	v_mfma_f32_16x16x32_bf16 v[36:39], v[218:221], v[226:229], v[36:39]
	ds_read_b128 v[226:229], v6 offset:15360
	s_waitcnt lgkmcnt(3)
	v_mfma_f32_16x16x32_bf16 v[104:107], v[158:161], v[166:169], v[104:107]
	v_mfma_f32_16x16x32_bf16 v[108:111], v[162:165], v[166:169], v[108:111]
	v_mfma_f32_16x16x32_bf16 v[112:115], v[214:217], v[166:169], v[112:115]
	v_mfma_f32_16x16x32_bf16 v[52:55], v[218:221], v[166:169], v[52:55]
	s_waitcnt lgkmcnt(2)
	v_mfma_f32_16x16x32_bf16 v[116:119], v[158:161], v[178:181], v[116:119]
	v_mfma_f32_16x16x32_bf16 v[120:123], v[162:165], v[178:181], v[120:123]
	v_mfma_f32_16x16x32_bf16 v[124:127], v[214:217], v[178:181], v[124:127]
	v_mfma_f32_16x16x32_bf16 v[68:71], v[218:221], v[178:181], v[68:71]
	s_waitcnt lgkmcnt(1)
	v_mfma_f32_16x16x32_bf16 v[128:131], v[158:161], v[222:225], v[128:131]
	v_mfma_f32_16x16x32_bf16 v[132:135], v[162:165], v[222:225], v[132:135]
	v_mfma_f32_16x16x32_bf16 v[136:139], v[214:217], v[222:225], v[136:139]
	v_mfma_f32_16x16x32_bf16 v[84:87], v[218:221], v[222:225], v[84:87]
	s_waitcnt lgkmcnt(0)
	v_mfma_f32_16x16x32_bf16 v[100:103], v[158:161], v[226:229], v[100:103]
	v_mfma_f32_16x16x32_bf16 v[140:143], v[162:165], v[226:229], v[140:143]
	v_mfma_f32_16x16x32_bf16 v[150:153], v[214:217], v[226:229], v[150:153]
	v_mfma_f32_16x16x32_bf16 v[154:157], v[218:221], v[226:229], v[154:157]
	s_add_u32 s64, s0, 0x800
	s_addc_u32 s65, s1, 0
	s_add_u32 s68, s14, 0x800
	s_waitcnt vmcnt(0)
	s_barrier
	s_addc_u32 s69, s15, 0
	ds_read_b128 v[158:161], v8
	ds_read_b128 v[162:165], v12
	ds_read_b128 v[166:169], v9
	ds_read_b128 v[178:181], v13
	ds_read_b128 v[214:217], v11
	ds_read_b128 v[218:221], v10
	ds_read_b128 v[222:225], v14
	ds_read_b128 v[226:229], v15
	s_waitcnt lgkmcnt(6)
	v_mfma_f32_16x16x32_bf16 v[40:43], v[158:161], v[162:165], v[40:43]
	s_waitcnt lgkmcnt(5)
	v_mfma_f32_16x16x32_bf16 v[44:47], v[166:169], v[162:165], v[44:47]
	s_waitcnt lgkmcnt(4)
	v_mfma_f32_16x16x32_bf16 v[56:59], v[158:161], v[178:181], v[56:59]
	s_mov_b32 m0, s42
	v_mfma_f32_16x16x32_bf16 v[60:63], v[166:169], v[178:181], v[60:63]
	global_load_lds_dwordx4 v0, s[64:65]
	s_waitcnt lgkmcnt(3)
	v_mfma_f32_16x16x32_bf16 v[48:51], v[214:217], v[162:165], v[48:51]
	v_mfma_f32_16x16x32_bf16 v[64:67], v[214:217], v[178:181], v[64:67]
	s_waitcnt lgkmcnt(2)
	v_mfma_f32_16x16x32_bf16 v[174:177], v[218:221], v[162:165], v[174:177]
	ds_read_b128 v[162:165], v16
	v_mfma_f32_16x16x32_bf16 v[170:173], v[218:221], v[178:181], v[170:173]
	ds_read_b128 v[178:181], v17
	s_waitcnt lgkmcnt(3)
	s_mov_b32 m0, s43
	v_mfma_f32_16x16x32_bf16 v[72:75], v[158:161], v[222:225], v[72:75]
	global_load_lds_dwordx4 v0, s[68:69]
	v_mfma_f32_16x16x32_bf16 v[76:79], v[166:169], v[222:225], v[76:79]
	v_mfma_f32_16x16x32_bf16 v[80:83], v[214:217], v[222:225], v[80:83]
	v_mfma_f32_16x16x32_bf16 v[32:35], v[218:221], v[222:225], v[32:35]
	ds_read_b128 v[222:225], v18
	s_waitcnt lgkmcnt(3)
	v_mfma_f32_16x16x32_bf16 v[88:91], v[158:161], v[226:229], v[88:91]
	s_mov_b32 m0, s44
	v_mfma_f32_16x16x32_bf16 v[92:95], v[166:169], v[226:229], v[92:95]
	global_load_lds_dwordx4 v2, s[64:65]
	v_mfma_f32_16x16x32_bf16 v[96:99], v[214:217], v[226:229], v[96:99]
	v_mfma_f32_16x16x32_bf16 v[36:39], v[218:221], v[226:229], v[36:39]
	ds_read_b128 v[226:229], v19
	s_waitcnt lgkmcnt(3)
	v_mfma_f32_16x16x32_bf16 v[104:107], v[158:161], v[162:165], v[104:107]
	s_waitcnt lgkmcnt(2)
	v_mfma_f32_16x16x32_bf16 v[116:119], v[158:161], v[178:181], v[116:119]
	s_waitcnt lgkmcnt(1)
	s_mov_b32 m0, s45
	v_mfma_f32_16x16x32_bf16 v[128:131], v[158:161], v[222:225], v[128:131]
	global_load_lds_dwordx4 v2, s[68:69]
	s_waitcnt lgkmcnt(0)
	v_mfma_f32_16x16x32_bf16 v[100:103], v[158:161], v[226:229], v[100:103]
	ds_read_b128 v[158:161], v20
	v_mfma_f32_16x16x32_bf16 v[108:111], v[166:169], v[162:165], v[108:111]
	v_mfma_f32_16x16x32_bf16 v[120:123], v[166:169], v[178:181], v[120:123]
	v_mfma_f32_16x16x32_bf16 v[132:135], v[166:169], v[222:225], v[132:135]
	s_mov_b32 m0, s46
	v_mfma_f32_16x16x32_bf16 v[140:143], v[166:169], v[226:229], v[140:143]
	global_load_lds_dwordx4 v4, s[64:65]
	ds_read_b128 v[166:169], v24
	v_mfma_f32_16x16x32_bf16 v[112:115], v[214:217], v[162:165], v[112:115]
	v_mfma_f32_16x16x32_bf16 v[52:55], v[218:221], v[162:165], v[52:55]
	ds_read_b128 v[162:165], v21
	v_mfma_f32_16x16x32_bf16 v[124:127], v[214:217], v[178:181], v[124:127]
	v_mfma_f32_16x16x32_bf16 v[68:71], v[218:221], v[178:181], v[68:71]
	ds_read_b128 v[178:181], v25
	s_mov_b32 m0, s47
	v_mfma_f32_16x16x32_bf16 v[136:139], v[214:217], v[222:225], v[136:139]
	global_load_lds_dwordx4 v4, s[68:69]
	v_mfma_f32_16x16x32_bf16 v[84:87], v[218:221], v[222:225], v[84:87]
	ds_read_b128 v[222:225], v26
	v_mfma_f32_16x16x32_bf16 v[150:153], v[214:217], v[226:229], v[150:153]
	ds_read_b128 v[214:217], v23
	v_mfma_f32_16x16x32_bf16 v[154:157], v[218:221], v[226:229], v[154:157]
	ds_read_b128 v[218:221], v22
	ds_read_b128 v[226:229], v27
	s_waitcnt lgkmcnt(6)
	v_mfma_f32_16x16x32_bf16 v[40:43], v[158:161], v[166:169], v[40:43]
	s_waitcnt lgkmcnt(5)
	s_mov_b32 m0, s49
	v_mfma_f32_16x16x32_bf16 v[44:47], v[162:165], v[166:169], v[44:47]
	global_load_lds_dwordx4 v146, s[64:65]
	s_waitcnt lgkmcnt(4)
	v_mfma_f32_16x16x32_bf16 v[56:59], v[158:161], v[178:181], v[56:59]
	v_mfma_f32_16x16x32_bf16 v[60:63], v[162:165], v[178:181], v[60:63]
	s_waitcnt lgkmcnt(3)
	v_mfma_f32_16x16x32_bf16 v[72:75], v[158:161], v[222:225], v[72:75]
	v_mfma_f32_16x16x32_bf16 v[76:79], v[162:165], v[222:225], v[76:79]
	s_waitcnt lgkmcnt(2)
	s_mov_b32 m0, s50
	v_mfma_f32_16x16x32_bf16 v[48:51], v[214:217], v[166:169], v[48:51]
	global_load_lds_dwordx4 v146, s[68:69]
	s_waitcnt lgkmcnt(1)
	v_mfma_f32_16x16x32_bf16 v[174:177], v[218:221], v[166:169], v[174:177]
	ds_read_b128 v[166:169], v28
	v_mfma_f32_16x16x32_bf16 v[64:67], v[214:217], v[178:181], v[64:67]
	v_mfma_f32_16x16x32_bf16 v[170:173], v[218:221], v[178:181], v[170:173]
	ds_read_b128 v[178:181], v29
	v_mfma_f32_16x16x32_bf16 v[80:83], v[214:217], v[222:225], v[80:83]
	v_mfma_f32_16x16x32_bf16 v[32:35], v[218:221], v[222:225], v[32:35]
	ds_read_b128 v[222:225], v30
	s_waitcnt lgkmcnt(3)
	v_mfma_f32_16x16x32_bf16 v[88:91], v[158:161], v[226:229], v[88:91]
	v_mfma_f32_16x16x32_bf16 v[92:95], v[162:165], v[226:229], v[92:95]
	v_mfma_f32_16x16x32_bf16 v[96:99], v[214:217], v[226:229], v[96:99]
	v_mfma_f32_16x16x32_bf16 v[36:39], v[218:221], v[226:229], v[36:39]
	ds_read_b128 v[226:229], v31
	s_waitcnt lgkmcnt(3)
	v_mfma_f32_16x16x32_bf16 v[104:107], v[158:161], v[166:169], v[104:107]
	v_mfma_f32_16x16x32_bf16 v[108:111], v[162:165], v[166:169], v[108:111]
	v_mfma_f32_16x16x32_bf16 v[112:115], v[214:217], v[166:169], v[112:115]
	v_mfma_f32_16x16x32_bf16 v[52:55], v[218:221], v[166:169], v[52:55]
	s_waitcnt lgkmcnt(2)
	v_mfma_f32_16x16x32_bf16 v[116:119], v[158:161], v[178:181], v[116:119]
	v_mfma_f32_16x16x32_bf16 v[120:123], v[162:165], v[178:181], v[120:123]
	v_mfma_f32_16x16x32_bf16 v[124:127], v[214:217], v[178:181], v[124:127]
	v_mfma_f32_16x16x32_bf16 v[68:71], v[218:221], v[178:181], v[68:71]
	s_waitcnt lgkmcnt(1)
	v_mfma_f32_16x16x32_bf16 v[128:131], v[158:161], v[222:225], v[128:131]
	v_mfma_f32_16x16x32_bf16 v[132:135], v[162:165], v[222:225], v[132:135]
	v_mfma_f32_16x16x32_bf16 v[136:139], v[214:217], v[222:225], v[136:139]
	v_mfma_f32_16x16x32_bf16 v[84:87], v[218:221], v[222:225], v[84:87]
	s_waitcnt lgkmcnt(0)
	v_mfma_f32_16x16x32_bf16 v[100:103], v[158:161], v[226:229], v[100:103]
	v_mfma_f32_16x16x32_bf16 v[140:143], v[162:165], v[226:229], v[140:143]
	v_mfma_f32_16x16x32_bf16 v[150:153], v[214:217], v[226:229], v[150:153]
	v_mfma_f32_16x16x32_bf16 v[154:157], v[218:221], v[226:229], v[154:157]
	s_add_u32 s64, s0, 0x880
	s_addc_u32 s65, s1, 0
	s_add_u32 s68, s14, 0x880
	s_waitcnt vmcnt(0)
	s_barrier
	s_addc_u32 s69, s15, 0
	ds_read_b128 v[158:161], v7 offset:32768
	ds_read_b128 v[162:165], v6
	ds_read_b128 v[166:169], v7 offset:34816
	ds_read_b128 v[178:181], v6 offset:2048
	ds_read_b128 v[214:217], v7 offset:36864
	ds_read_b128 v[218:221], v7 offset:38912
	ds_read_b128 v[222:225], v6 offset:4096
	ds_read_b128 v[226:229], v6 offset:6144
	s_waitcnt lgkmcnt(6)
	v_mfma_f32_16x16x32_bf16 v[40:43], v[158:161], v[162:165], v[40:43]
	s_waitcnt lgkmcnt(5)
	v_mfma_f32_16x16x32_bf16 v[44:47], v[166:169], v[162:165], v[44:47]
	s_waitcnt lgkmcnt(4)
	v_mfma_f32_16x16x32_bf16 v[56:59], v[158:161], v[178:181], v[56:59]
	s_mov_b32 m0, s52
	v_mfma_f32_16x16x32_bf16 v[60:63], v[166:169], v[178:181], v[60:63]
	global_load_lds_dwordx4 v0, s[64:65]
	s_waitcnt lgkmcnt(3)
	v_mfma_f32_16x16x32_bf16 v[48:51], v[214:217], v[162:165], v[48:51]
	v_mfma_f32_16x16x32_bf16 v[64:67], v[214:217], v[178:181], v[64:67]
	s_waitcnt lgkmcnt(2)
	v_mfma_f32_16x16x32_bf16 v[174:177], v[218:221], v[162:165], v[174:177]
	ds_read_b128 v[162:165], v6 offset:8192
	v_mfma_f32_16x16x32_bf16 v[170:173], v[218:221], v[178:181], v[170:173]
	ds_read_b128 v[178:181], v6 offset:10240
	s_waitcnt lgkmcnt(3)
	s_mov_b32 m0, s51
	v_mfma_f32_16x16x32_bf16 v[72:75], v[158:161], v[222:225], v[72:75]
	global_load_lds_dwordx4 v0, s[68:69]
	v_mfma_f32_16x16x32_bf16 v[76:79], v[166:169], v[222:225], v[76:79]
	v_mfma_f32_16x16x32_bf16 v[80:83], v[214:217], v[222:225], v[80:83]
	v_mfma_f32_16x16x32_bf16 v[32:35], v[218:221], v[222:225], v[32:35]
	ds_read_b128 v[222:225], v6 offset:12288
	s_waitcnt lgkmcnt(3)
	v_mfma_f32_16x16x32_bf16 v[88:91], v[158:161], v[226:229], v[88:91]
	s_mov_b32 m0, s53
	v_mfma_f32_16x16x32_bf16 v[92:95], v[166:169], v[226:229], v[92:95]
	global_load_lds_dwordx4 v2, s[64:65]
	v_mfma_f32_16x16x32_bf16 v[96:99], v[214:217], v[226:229], v[96:99]
	v_mfma_f32_16x16x32_bf16 v[36:39], v[218:221], v[226:229], v[36:39]
	ds_read_b128 v[226:229], v6 offset:14336
	s_waitcnt lgkmcnt(3)
	v_mfma_f32_16x16x32_bf16 v[104:107], v[158:161], v[162:165], v[104:107]
	s_waitcnt lgkmcnt(2)
	v_mfma_f32_16x16x32_bf16 v[116:119], v[158:161], v[178:181], v[116:119]
	s_waitcnt lgkmcnt(1)
	s_mov_b32 m0, s54
	v_mfma_f32_16x16x32_bf16 v[128:131], v[158:161], v[222:225], v[128:131]
	global_load_lds_dwordx4 v2, s[68:69]
	s_waitcnt lgkmcnt(0)
	v_mfma_f32_16x16x32_bf16 v[100:103], v[158:161], v[226:229], v[100:103]
	ds_read_b128 v[158:161], v7 offset:33792
	v_mfma_f32_16x16x32_bf16 v[108:111], v[166:169], v[162:165], v[108:111]
	v_mfma_f32_16x16x32_bf16 v[120:123], v[166:169], v[178:181], v[120:123]
	v_mfma_f32_16x16x32_bf16 v[132:135], v[166:169], v[222:225], v[132:135]
	s_mov_b32 m0, s55
	v_mfma_f32_16x16x32_bf16 v[140:143], v[166:169], v[226:229], v[140:143]
	global_load_lds_dwordx4 v4, s[64:65]
	ds_read_b128 v[166:169], v6 offset:1024
	v_mfma_f32_16x16x32_bf16 v[112:115], v[214:217], v[162:165], v[112:115]
	v_mfma_f32_16x16x32_bf16 v[52:55], v[218:221], v[162:165], v[52:55]
	ds_read_b128 v[162:165], v7 offset:35840
	v_mfma_f32_16x16x32_bf16 v[124:127], v[214:217], v[178:181], v[124:127]
	v_mfma_f32_16x16x32_bf16 v[68:71], v[218:221], v[178:181], v[68:71]
	ds_read_b128 v[178:181], v6 offset:3072
	s_mov_b32 m0, s58
	v_mfma_f32_16x16x32_bf16 v[136:139], v[214:217], v[222:225], v[136:139]
	global_load_lds_dwordx4 v4, s[68:69]
	v_mfma_f32_16x16x32_bf16 v[84:87], v[218:221], v[222:225], v[84:87]
	ds_read_b128 v[222:225], v6 offset:5120
	v_mfma_f32_16x16x32_bf16 v[150:153], v[214:217], v[226:229], v[150:153]
	ds_read_b128 v[214:217], v7 offset:37888
	v_mfma_f32_16x16x32_bf16 v[154:157], v[218:221], v[226:229], v[154:157]
	ds_read_b128 v[218:221], v7 offset:39936
	ds_read_b128 v[226:229], v6 offset:7168
	s_waitcnt lgkmcnt(6)
	v_mfma_f32_16x16x32_bf16 v[40:43], v[158:161], v[166:169], v[40:43]
	s_waitcnt lgkmcnt(5)
	s_mov_b32 m0, s62
	v_mfma_f32_16x16x32_bf16 v[44:47], v[162:165], v[166:169], v[44:47]
	global_load_lds_dwordx4 v146, s[64:65]
	s_waitcnt lgkmcnt(4)
	v_mfma_f32_16x16x32_bf16 v[56:59], v[158:161], v[178:181], v[56:59]
	v_mfma_f32_16x16x32_bf16 v[60:63], v[162:165], v[178:181], v[60:63]
	s_waitcnt lgkmcnt(3)
	v_mfma_f32_16x16x32_bf16 v[72:75], v[158:161], v[222:225], v[72:75]
	v_mfma_f32_16x16x32_bf16 v[76:79], v[162:165], v[222:225], v[76:79]
	s_waitcnt lgkmcnt(2)
	s_mov_b32 m0, s63
	v_mfma_f32_16x16x32_bf16 v[48:51], v[214:217], v[166:169], v[48:51]
	global_load_lds_dwordx4 v146, s[68:69]
	s_waitcnt lgkmcnt(1)
	v_mfma_f32_16x16x32_bf16 v[174:177], v[218:221], v[166:169], v[174:177]
	ds_read_b128 v[166:169], v6 offset:9216
	v_mfma_f32_16x16x32_bf16 v[64:67], v[214:217], v[178:181], v[64:67]
	v_mfma_f32_16x16x32_bf16 v[170:173], v[218:221], v[178:181], v[170:173]
	ds_read_b128 v[178:181], v6 offset:11264
	v_mfma_f32_16x16x32_bf16 v[80:83], v[214:217], v[222:225], v[80:83]
	v_mfma_f32_16x16x32_bf16 v[32:35], v[218:221], v[222:225], v[32:35]
	ds_read_b128 v[222:225], v6 offset:13312
	s_waitcnt lgkmcnt(3)
	v_mfma_f32_16x16x32_bf16 v[88:91], v[158:161], v[226:229], v[88:91]
	v_mfma_f32_16x16x32_bf16 v[92:95], v[162:165], v[226:229], v[92:95]
	v_mfma_f32_16x16x32_bf16 v[96:99], v[214:217], v[226:229], v[96:99]
	v_mfma_f32_16x16x32_bf16 v[36:39], v[218:221], v[226:229], v[36:39]
	ds_read_b128 v[226:229], v6 offset:15360
	s_waitcnt lgkmcnt(3)
	v_mfma_f32_16x16x32_bf16 v[104:107], v[158:161], v[166:169], v[104:107]
	v_mfma_f32_16x16x32_bf16 v[108:111], v[162:165], v[166:169], v[108:111]
	v_mfma_f32_16x16x32_bf16 v[112:115], v[214:217], v[166:169], v[112:115]
	v_mfma_f32_16x16x32_bf16 v[52:55], v[218:221], v[166:169], v[52:55]
	s_waitcnt lgkmcnt(2)
	v_mfma_f32_16x16x32_bf16 v[116:119], v[158:161], v[178:181], v[116:119]
	v_mfma_f32_16x16x32_bf16 v[120:123], v[162:165], v[178:181], v[120:123]
	v_mfma_f32_16x16x32_bf16 v[124:127], v[214:217], v[178:181], v[124:127]
	v_mfma_f32_16x16x32_bf16 v[68:71], v[218:221], v[178:181], v[68:71]
	s_waitcnt lgkmcnt(1)
	v_mfma_f32_16x16x32_bf16 v[128:131], v[158:161], v[222:225], v[128:131]
	v_mfma_f32_16x16x32_bf16 v[132:135], v[162:165], v[222:225], v[132:135]
	v_mfma_f32_16x16x32_bf16 v[136:139], v[214:217], v[222:225], v[136:139]
	v_mfma_f32_16x16x32_bf16 v[84:87], v[218:221], v[222:225], v[84:87]
	s_waitcnt lgkmcnt(0)
	v_mfma_f32_16x16x32_bf16 v[100:103], v[158:161], v[226:229], v[100:103]
	v_mfma_f32_16x16x32_bf16 v[140:143], v[162:165], v[226:229], v[140:143]
	v_mfma_f32_16x16x32_bf16 v[150:153], v[214:217], v[226:229], v[150:153]
	v_mfma_f32_16x16x32_bf16 v[154:157], v[218:221], v[226:229], v[154:157]
	s_add_u32 s64, s0, 0x900
	s_addc_u32 s65, s1, 0
	s_add_u32 s68, s14, 0x900
	s_waitcnt vmcnt(0)
	s_barrier
	s_addc_u32 s69, s15, 0
	ds_read_b128 v[158:161], v8
	ds_read_b128 v[162:165], v12
	ds_read_b128 v[166:169], v9
	ds_read_b128 v[178:181], v13
	ds_read_b128 v[214:217], v11
	ds_read_b128 v[218:221], v10
	ds_read_b128 v[222:225], v14
	ds_read_b128 v[226:229], v15
	s_waitcnt lgkmcnt(6)
	v_mfma_f32_16x16x32_bf16 v[40:43], v[158:161], v[162:165], v[40:43]
	s_waitcnt lgkmcnt(5)
	v_mfma_f32_16x16x32_bf16 v[44:47], v[166:169], v[162:165], v[44:47]
	s_waitcnt lgkmcnt(4)
	v_mfma_f32_16x16x32_bf16 v[56:59], v[158:161], v[178:181], v[56:59]
	s_mov_b32 m0, s42
	v_mfma_f32_16x16x32_bf16 v[60:63], v[166:169], v[178:181], v[60:63]
	global_load_lds_dwordx4 v0, s[64:65]
	s_waitcnt lgkmcnt(3)
	v_mfma_f32_16x16x32_bf16 v[48:51], v[214:217], v[162:165], v[48:51]
	v_mfma_f32_16x16x32_bf16 v[64:67], v[214:217], v[178:181], v[64:67]
	s_waitcnt lgkmcnt(2)
	v_mfma_f32_16x16x32_bf16 v[174:177], v[218:221], v[162:165], v[174:177]
	ds_read_b128 v[162:165], v16
	v_mfma_f32_16x16x32_bf16 v[170:173], v[218:221], v[178:181], v[170:173]
	ds_read_b128 v[178:181], v17
	s_waitcnt lgkmcnt(3)
	s_mov_b32 m0, s43
	v_mfma_f32_16x16x32_bf16 v[72:75], v[158:161], v[222:225], v[72:75]
	global_load_lds_dwordx4 v0, s[68:69]
	v_mfma_f32_16x16x32_bf16 v[76:79], v[166:169], v[222:225], v[76:79]
	v_mfma_f32_16x16x32_bf16 v[80:83], v[214:217], v[222:225], v[80:83]
	v_mfma_f32_16x16x32_bf16 v[32:35], v[218:221], v[222:225], v[32:35]
	ds_read_b128 v[222:225], v18
	s_waitcnt lgkmcnt(3)
	v_mfma_f32_16x16x32_bf16 v[88:91], v[158:161], v[226:229], v[88:91]
	s_mov_b32 m0, s44
	v_mfma_f32_16x16x32_bf16 v[92:95], v[166:169], v[226:229], v[92:95]
	global_load_lds_dwordx4 v2, s[64:65]
	v_mfma_f32_16x16x32_bf16 v[96:99], v[214:217], v[226:229], v[96:99]
	v_mfma_f32_16x16x32_bf16 v[36:39], v[218:221], v[226:229], v[36:39]
	ds_read_b128 v[226:229], v19
	s_waitcnt lgkmcnt(3)
	v_mfma_f32_16x16x32_bf16 v[104:107], v[158:161], v[162:165], v[104:107]
	s_waitcnt lgkmcnt(2)
	v_mfma_f32_16x16x32_bf16 v[116:119], v[158:161], v[178:181], v[116:119]
	s_waitcnt lgkmcnt(1)
	s_mov_b32 m0, s45
	v_mfma_f32_16x16x32_bf16 v[128:131], v[158:161], v[222:225], v[128:131]
	global_load_lds_dwordx4 v2, s[68:69]
	s_waitcnt lgkmcnt(0)
	v_mfma_f32_16x16x32_bf16 v[100:103], v[158:161], v[226:229], v[100:103]
	ds_read_b128 v[158:161], v20
	v_mfma_f32_16x16x32_bf16 v[108:111], v[166:169], v[162:165], v[108:111]
	v_mfma_f32_16x16x32_bf16 v[120:123], v[166:169], v[178:181], v[120:123]
	v_mfma_f32_16x16x32_bf16 v[132:135], v[166:169], v[222:225], v[132:135]
	s_mov_b32 m0, s46
	v_mfma_f32_16x16x32_bf16 v[140:143], v[166:169], v[226:229], v[140:143]
	global_load_lds_dwordx4 v4, s[64:65]
	ds_read_b128 v[166:169], v24
	v_mfma_f32_16x16x32_bf16 v[112:115], v[214:217], v[162:165], v[112:115]
	v_mfma_f32_16x16x32_bf16 v[52:55], v[218:221], v[162:165], v[52:55]
	ds_read_b128 v[162:165], v21
	v_mfma_f32_16x16x32_bf16 v[124:127], v[214:217], v[178:181], v[124:127]
	v_mfma_f32_16x16x32_bf16 v[68:71], v[218:221], v[178:181], v[68:71]
	ds_read_b128 v[178:181], v25
	s_mov_b32 m0, s47
	v_mfma_f32_16x16x32_bf16 v[136:139], v[214:217], v[222:225], v[136:139]
	global_load_lds_dwordx4 v4, s[68:69]
	v_mfma_f32_16x16x32_bf16 v[84:87], v[218:221], v[222:225], v[84:87]
	ds_read_b128 v[222:225], v26
	v_mfma_f32_16x16x32_bf16 v[150:153], v[214:217], v[226:229], v[150:153]
	ds_read_b128 v[214:217], v23
	v_mfma_f32_16x16x32_bf16 v[154:157], v[218:221], v[226:229], v[154:157]
	ds_read_b128 v[218:221], v22
	ds_read_b128 v[226:229], v27
	s_waitcnt lgkmcnt(6)
	v_mfma_f32_16x16x32_bf16 v[40:43], v[158:161], v[166:169], v[40:43]
	s_waitcnt lgkmcnt(5)
	s_mov_b32 m0, s49
	v_mfma_f32_16x16x32_bf16 v[44:47], v[162:165], v[166:169], v[44:47]
	global_load_lds_dwordx4 v146, s[64:65]
	s_waitcnt lgkmcnt(4)
	v_mfma_f32_16x16x32_bf16 v[56:59], v[158:161], v[178:181], v[56:59]
	v_mfma_f32_16x16x32_bf16 v[60:63], v[162:165], v[178:181], v[60:63]
	s_waitcnt lgkmcnt(3)
	v_mfma_f32_16x16x32_bf16 v[72:75], v[158:161], v[222:225], v[72:75]
	v_mfma_f32_16x16x32_bf16 v[76:79], v[162:165], v[222:225], v[76:79]
	s_waitcnt lgkmcnt(2)
	s_mov_b32 m0, s50
	v_mfma_f32_16x16x32_bf16 v[48:51], v[214:217], v[166:169], v[48:51]
	global_load_lds_dwordx4 v146, s[68:69]
	s_waitcnt lgkmcnt(1)
	v_mfma_f32_16x16x32_bf16 v[174:177], v[218:221], v[166:169], v[174:177]
	ds_read_b128 v[166:169], v28
	v_mfma_f32_16x16x32_bf16 v[64:67], v[214:217], v[178:181], v[64:67]
	v_mfma_f32_16x16x32_bf16 v[170:173], v[218:221], v[178:181], v[170:173]
	ds_read_b128 v[178:181], v29
	v_mfma_f32_16x16x32_bf16 v[80:83], v[214:217], v[222:225], v[80:83]
	v_mfma_f32_16x16x32_bf16 v[32:35], v[218:221], v[222:225], v[32:35]
	ds_read_b128 v[222:225], v30
	s_waitcnt lgkmcnt(3)
	v_mfma_f32_16x16x32_bf16 v[88:91], v[158:161], v[226:229], v[88:91]
	v_mfma_f32_16x16x32_bf16 v[92:95], v[162:165], v[226:229], v[92:95]
	v_mfma_f32_16x16x32_bf16 v[96:99], v[214:217], v[226:229], v[96:99]
	v_mfma_f32_16x16x32_bf16 v[36:39], v[218:221], v[226:229], v[36:39]
	ds_read_b128 v[226:229], v31
	s_waitcnt lgkmcnt(3)
	v_mfma_f32_16x16x32_bf16 v[104:107], v[158:161], v[166:169], v[104:107]
	v_mfma_f32_16x16x32_bf16 v[108:111], v[162:165], v[166:169], v[108:111]
	v_mfma_f32_16x16x32_bf16 v[112:115], v[214:217], v[166:169], v[112:115]
	v_mfma_f32_16x16x32_bf16 v[52:55], v[218:221], v[166:169], v[52:55]
	s_waitcnt lgkmcnt(2)
	v_mfma_f32_16x16x32_bf16 v[116:119], v[158:161], v[178:181], v[116:119]
	v_mfma_f32_16x16x32_bf16 v[120:123], v[162:165], v[178:181], v[120:123]
	v_mfma_f32_16x16x32_bf16 v[124:127], v[214:217], v[178:181], v[124:127]
	v_mfma_f32_16x16x32_bf16 v[68:71], v[218:221], v[178:181], v[68:71]
	s_waitcnt lgkmcnt(1)
	v_mfma_f32_16x16x32_bf16 v[128:131], v[158:161], v[222:225], v[128:131]
	v_mfma_f32_16x16x32_bf16 v[132:135], v[162:165], v[222:225], v[132:135]
	v_mfma_f32_16x16x32_bf16 v[136:139], v[214:217], v[222:225], v[136:139]
	v_mfma_f32_16x16x32_bf16 v[84:87], v[218:221], v[222:225], v[84:87]
	s_waitcnt lgkmcnt(0)
	v_mfma_f32_16x16x32_bf16 v[100:103], v[158:161], v[226:229], v[100:103]
	v_mfma_f32_16x16x32_bf16 v[140:143], v[162:165], v[226:229], v[140:143]
	v_mfma_f32_16x16x32_bf16 v[150:153], v[214:217], v[226:229], v[150:153]
	v_mfma_f32_16x16x32_bf16 v[154:157], v[218:221], v[226:229], v[154:157]
	s_add_u32 s64, s0, 0x980
	s_addc_u32 s65, s1, 0
	s_add_u32 s68, s14, 0x980
	s_waitcnt vmcnt(0)
	s_barrier
	s_addc_u32 s69, s15, 0
	ds_read_b128 v[158:161], v7 offset:32768
	ds_read_b128 v[162:165], v6
	ds_read_b128 v[166:169], v7 offset:34816
	ds_read_b128 v[178:181], v6 offset:2048
	ds_read_b128 v[214:217], v7 offset:36864
	ds_read_b128 v[218:221], v7 offset:38912
	ds_read_b128 v[222:225], v6 offset:4096
	ds_read_b128 v[226:229], v6 offset:6144
	s_waitcnt lgkmcnt(6)
	v_mfma_f32_16x16x32_bf16 v[40:43], v[158:161], v[162:165], v[40:43]
	s_waitcnt lgkmcnt(5)
	v_mfma_f32_16x16x32_bf16 v[44:47], v[166:169], v[162:165], v[44:47]
	s_waitcnt lgkmcnt(4)
	v_mfma_f32_16x16x32_bf16 v[56:59], v[158:161], v[178:181], v[56:59]
	s_mov_b32 m0, s52
	v_mfma_f32_16x16x32_bf16 v[60:63], v[166:169], v[178:181], v[60:63]
	global_load_lds_dwordx4 v0, s[64:65]
	s_waitcnt lgkmcnt(3)
	v_mfma_f32_16x16x32_bf16 v[48:51], v[214:217], v[162:165], v[48:51]
	v_mfma_f32_16x16x32_bf16 v[64:67], v[214:217], v[178:181], v[64:67]
	s_waitcnt lgkmcnt(2)
	v_mfma_f32_16x16x32_bf16 v[174:177], v[218:221], v[162:165], v[174:177]
	ds_read_b128 v[162:165], v6 offset:8192
	v_mfma_f32_16x16x32_bf16 v[170:173], v[218:221], v[178:181], v[170:173]
	ds_read_b128 v[178:181], v6 offset:10240
	s_waitcnt lgkmcnt(3)
	s_mov_b32 m0, s51
	v_mfma_f32_16x16x32_bf16 v[72:75], v[158:161], v[222:225], v[72:75]
	global_load_lds_dwordx4 v0, s[68:69]
	v_mfma_f32_16x16x32_bf16 v[76:79], v[166:169], v[222:225], v[76:79]
	v_mfma_f32_16x16x32_bf16 v[80:83], v[214:217], v[222:225], v[80:83]
	v_mfma_f32_16x16x32_bf16 v[32:35], v[218:221], v[222:225], v[32:35]
	ds_read_b128 v[222:225], v6 offset:12288
	s_waitcnt lgkmcnt(3)
	v_mfma_f32_16x16x32_bf16 v[88:91], v[158:161], v[226:229], v[88:91]
	s_mov_b32 m0, s53
	v_mfma_f32_16x16x32_bf16 v[92:95], v[166:169], v[226:229], v[92:95]
	global_load_lds_dwordx4 v2, s[64:65]
	v_mfma_f32_16x16x32_bf16 v[96:99], v[214:217], v[226:229], v[96:99]
	v_mfma_f32_16x16x32_bf16 v[36:39], v[218:221], v[226:229], v[36:39]
	ds_read_b128 v[226:229], v6 offset:14336
	s_waitcnt lgkmcnt(3)
	v_mfma_f32_16x16x32_bf16 v[104:107], v[158:161], v[162:165], v[104:107]
	s_waitcnt lgkmcnt(2)
	v_mfma_f32_16x16x32_bf16 v[116:119], v[158:161], v[178:181], v[116:119]
	s_waitcnt lgkmcnt(1)
	s_mov_b32 m0, s54
	v_mfma_f32_16x16x32_bf16 v[128:131], v[158:161], v[222:225], v[128:131]
	global_load_lds_dwordx4 v2, s[68:69]
	s_waitcnt lgkmcnt(0)
	v_mfma_f32_16x16x32_bf16 v[100:103], v[158:161], v[226:229], v[100:103]
	ds_read_b128 v[158:161], v7 offset:33792
	v_mfma_f32_16x16x32_bf16 v[108:111], v[166:169], v[162:165], v[108:111]
	v_mfma_f32_16x16x32_bf16 v[120:123], v[166:169], v[178:181], v[120:123]
	v_mfma_f32_16x16x32_bf16 v[132:135], v[166:169], v[222:225], v[132:135]
	s_mov_b32 m0, s55
	v_mfma_f32_16x16x32_bf16 v[140:143], v[166:169], v[226:229], v[140:143]
	global_load_lds_dwordx4 v4, s[64:65]
	ds_read_b128 v[166:169], v6 offset:1024
	v_mfma_f32_16x16x32_bf16 v[112:115], v[214:217], v[162:165], v[112:115]
	v_mfma_f32_16x16x32_bf16 v[52:55], v[218:221], v[162:165], v[52:55]
	ds_read_b128 v[162:165], v7 offset:35840
	v_mfma_f32_16x16x32_bf16 v[124:127], v[214:217], v[178:181], v[124:127]
	v_mfma_f32_16x16x32_bf16 v[68:71], v[218:221], v[178:181], v[68:71]
	ds_read_b128 v[178:181], v6 offset:3072
	s_mov_b32 m0, s58
	v_mfma_f32_16x16x32_bf16 v[136:139], v[214:217], v[222:225], v[136:139]
	global_load_lds_dwordx4 v4, s[68:69]
	v_mfma_f32_16x16x32_bf16 v[84:87], v[218:221], v[222:225], v[84:87]
	ds_read_b128 v[222:225], v6 offset:5120
	v_mfma_f32_16x16x32_bf16 v[150:153], v[214:217], v[226:229], v[150:153]
	ds_read_b128 v[214:217], v7 offset:37888
	v_mfma_f32_16x16x32_bf16 v[154:157], v[218:221], v[226:229], v[154:157]
	ds_read_b128 v[218:221], v7 offset:39936
	ds_read_b128 v[226:229], v6 offset:7168
	s_waitcnt lgkmcnt(6)
	v_mfma_f32_16x16x32_bf16 v[40:43], v[158:161], v[166:169], v[40:43]
	s_waitcnt lgkmcnt(5)
	s_mov_b32 m0, s62
	v_mfma_f32_16x16x32_bf16 v[44:47], v[162:165], v[166:169], v[44:47]
	global_load_lds_dwordx4 v146, s[64:65]
	s_waitcnt lgkmcnt(4)
	v_mfma_f32_16x16x32_bf16 v[56:59], v[158:161], v[178:181], v[56:59]
	v_mfma_f32_16x16x32_bf16 v[60:63], v[162:165], v[178:181], v[60:63]
	s_waitcnt lgkmcnt(3)
	v_mfma_f32_16x16x32_bf16 v[72:75], v[158:161], v[222:225], v[72:75]
	v_mfma_f32_16x16x32_bf16 v[76:79], v[162:165], v[222:225], v[76:79]
	s_waitcnt lgkmcnt(2)
	s_mov_b32 m0, s63
	v_mfma_f32_16x16x32_bf16 v[48:51], v[214:217], v[166:169], v[48:51]
	global_load_lds_dwordx4 v146, s[68:69]
	s_waitcnt lgkmcnt(1)
	v_mfma_f32_16x16x32_bf16 v[174:177], v[218:221], v[166:169], v[174:177]
	ds_read_b128 v[166:169], v6 offset:9216
	v_mfma_f32_16x16x32_bf16 v[64:67], v[214:217], v[178:181], v[64:67]
	v_mfma_f32_16x16x32_bf16 v[170:173], v[218:221], v[178:181], v[170:173]
	ds_read_b128 v[178:181], v6 offset:11264
	v_mfma_f32_16x16x32_bf16 v[80:83], v[214:217], v[222:225], v[80:83]
	v_mfma_f32_16x16x32_bf16 v[32:35], v[218:221], v[222:225], v[32:35]
	ds_read_b128 v[222:225], v6 offset:13312
	s_waitcnt lgkmcnt(3)
	v_mfma_f32_16x16x32_bf16 v[88:91], v[158:161], v[226:229], v[88:91]
	v_mfma_f32_16x16x32_bf16 v[92:95], v[162:165], v[226:229], v[92:95]
	v_mfma_f32_16x16x32_bf16 v[96:99], v[214:217], v[226:229], v[96:99]
	v_mfma_f32_16x16x32_bf16 v[36:39], v[218:221], v[226:229], v[36:39]
	ds_read_b128 v[226:229], v6 offset:15360
	s_waitcnt lgkmcnt(3)
	v_mfma_f32_16x16x32_bf16 v[104:107], v[158:161], v[166:169], v[104:107]
	v_mfma_f32_16x16x32_bf16 v[108:111], v[162:165], v[166:169], v[108:111]
	v_mfma_f32_16x16x32_bf16 v[112:115], v[214:217], v[166:169], v[112:115]
	v_mfma_f32_16x16x32_bf16 v[52:55], v[218:221], v[166:169], v[52:55]
	s_waitcnt lgkmcnt(2)
	v_mfma_f32_16x16x32_bf16 v[116:119], v[158:161], v[178:181], v[116:119]
	v_mfma_f32_16x16x32_bf16 v[120:123], v[162:165], v[178:181], v[120:123]
	v_mfma_f32_16x16x32_bf16 v[124:127], v[214:217], v[178:181], v[124:127]
	v_mfma_f32_16x16x32_bf16 v[68:71], v[218:221], v[178:181], v[68:71]
	s_waitcnt lgkmcnt(1)
	v_mfma_f32_16x16x32_bf16 v[128:131], v[158:161], v[222:225], v[128:131]
	v_mfma_f32_16x16x32_bf16 v[132:135], v[162:165], v[222:225], v[132:135]
	v_mfma_f32_16x16x32_bf16 v[136:139], v[214:217], v[222:225], v[136:139]
	v_mfma_f32_16x16x32_bf16 v[84:87], v[218:221], v[222:225], v[84:87]
	s_waitcnt lgkmcnt(0)
	v_mfma_f32_16x16x32_bf16 v[100:103], v[158:161], v[226:229], v[100:103]
	v_mfma_f32_16x16x32_bf16 v[140:143], v[162:165], v[226:229], v[140:143]
	v_mfma_f32_16x16x32_bf16 v[150:153], v[214:217], v[226:229], v[150:153]
	v_mfma_f32_16x16x32_bf16 v[154:157], v[218:221], v[226:229], v[154:157]
	s_add_u32 s64, s0, 0xa00
	s_addc_u32 s65, s1, 0
	s_add_u32 s68, s14, 0xa00
	s_waitcnt vmcnt(0)
	s_barrier
	s_addc_u32 s69, s15, 0
	ds_read_b128 v[158:161], v8
	ds_read_b128 v[162:165], v12
	ds_read_b128 v[166:169], v9
	ds_read_b128 v[178:181], v13
	ds_read_b128 v[214:217], v11
	ds_read_b128 v[218:221], v10
	ds_read_b128 v[222:225], v14
	ds_read_b128 v[226:229], v15
	s_waitcnt lgkmcnt(6)
	v_mfma_f32_16x16x32_bf16 v[40:43], v[158:161], v[162:165], v[40:43]
	s_waitcnt lgkmcnt(5)
	v_mfma_f32_16x16x32_bf16 v[44:47], v[166:169], v[162:165], v[44:47]
	s_waitcnt lgkmcnt(4)
	v_mfma_f32_16x16x32_bf16 v[56:59], v[158:161], v[178:181], v[56:59]
	s_mov_b32 m0, s42
	v_mfma_f32_16x16x32_bf16 v[60:63], v[166:169], v[178:181], v[60:63]
	global_load_lds_dwordx4 v0, s[64:65]
	s_waitcnt lgkmcnt(3)
	v_mfma_f32_16x16x32_bf16 v[48:51], v[214:217], v[162:165], v[48:51]
	v_mfma_f32_16x16x32_bf16 v[64:67], v[214:217], v[178:181], v[64:67]
	s_waitcnt lgkmcnt(2)
	v_mfma_f32_16x16x32_bf16 v[174:177], v[218:221], v[162:165], v[174:177]
	ds_read_b128 v[162:165], v16
	v_mfma_f32_16x16x32_bf16 v[170:173], v[218:221], v[178:181], v[170:173]
	ds_read_b128 v[178:181], v17
	s_waitcnt lgkmcnt(3)
	s_mov_b32 m0, s43
	v_mfma_f32_16x16x32_bf16 v[72:75], v[158:161], v[222:225], v[72:75]
	global_load_lds_dwordx4 v0, s[68:69]
	v_mfma_f32_16x16x32_bf16 v[76:79], v[166:169], v[222:225], v[76:79]
	v_mfma_f32_16x16x32_bf16 v[80:83], v[214:217], v[222:225], v[80:83]
	v_mfma_f32_16x16x32_bf16 v[32:35], v[218:221], v[222:225], v[32:35]
	ds_read_b128 v[222:225], v18
	s_waitcnt lgkmcnt(3)
	v_mfma_f32_16x16x32_bf16 v[88:91], v[158:161], v[226:229], v[88:91]
	s_mov_b32 m0, s44
	v_mfma_f32_16x16x32_bf16 v[92:95], v[166:169], v[226:229], v[92:95]
	global_load_lds_dwordx4 v2, s[64:65]
	v_mfma_f32_16x16x32_bf16 v[96:99], v[214:217], v[226:229], v[96:99]
	v_mfma_f32_16x16x32_bf16 v[36:39], v[218:221], v[226:229], v[36:39]
	ds_read_b128 v[226:229], v19
	s_waitcnt lgkmcnt(3)
	v_mfma_f32_16x16x32_bf16 v[104:107], v[158:161], v[162:165], v[104:107]
	s_waitcnt lgkmcnt(2)
	v_mfma_f32_16x16x32_bf16 v[116:119], v[158:161], v[178:181], v[116:119]
	s_waitcnt lgkmcnt(1)
	s_mov_b32 m0, s45
	v_mfma_f32_16x16x32_bf16 v[128:131], v[158:161], v[222:225], v[128:131]
	global_load_lds_dwordx4 v2, s[68:69]
	s_waitcnt lgkmcnt(0)
	v_mfma_f32_16x16x32_bf16 v[100:103], v[158:161], v[226:229], v[100:103]
	ds_read_b128 v[158:161], v20
	v_mfma_f32_16x16x32_bf16 v[108:111], v[166:169], v[162:165], v[108:111]
	v_mfma_f32_16x16x32_bf16 v[120:123], v[166:169], v[178:181], v[120:123]
	v_mfma_f32_16x16x32_bf16 v[132:135], v[166:169], v[222:225], v[132:135]
	s_mov_b32 m0, s46
	v_mfma_f32_16x16x32_bf16 v[140:143], v[166:169], v[226:229], v[140:143]
	global_load_lds_dwordx4 v4, s[64:65]
	ds_read_b128 v[166:169], v24
	v_mfma_f32_16x16x32_bf16 v[112:115], v[214:217], v[162:165], v[112:115]
	v_mfma_f32_16x16x32_bf16 v[52:55], v[218:221], v[162:165], v[52:55]
	ds_read_b128 v[162:165], v21
	v_mfma_f32_16x16x32_bf16 v[124:127], v[214:217], v[178:181], v[124:127]
	v_mfma_f32_16x16x32_bf16 v[68:71], v[218:221], v[178:181], v[68:71]
	ds_read_b128 v[178:181], v25
	s_mov_b32 m0, s47
	v_mfma_f32_16x16x32_bf16 v[136:139], v[214:217], v[222:225], v[136:139]
	global_load_lds_dwordx4 v4, s[68:69]
	v_mfma_f32_16x16x32_bf16 v[84:87], v[218:221], v[222:225], v[84:87]
	ds_read_b128 v[222:225], v26
	v_mfma_f32_16x16x32_bf16 v[150:153], v[214:217], v[226:229], v[150:153]
	ds_read_b128 v[214:217], v23
	v_mfma_f32_16x16x32_bf16 v[154:157], v[218:221], v[226:229], v[154:157]
	ds_read_b128 v[218:221], v22
	ds_read_b128 v[226:229], v27
	s_waitcnt lgkmcnt(6)
	v_mfma_f32_16x16x32_bf16 v[40:43], v[158:161], v[166:169], v[40:43]
	s_waitcnt lgkmcnt(5)
	s_mov_b32 m0, s49
	v_mfma_f32_16x16x32_bf16 v[44:47], v[162:165], v[166:169], v[44:47]
	global_load_lds_dwordx4 v146, s[64:65]
	s_waitcnt lgkmcnt(4)
	v_mfma_f32_16x16x32_bf16 v[56:59], v[158:161], v[178:181], v[56:59]
	v_mfma_f32_16x16x32_bf16 v[60:63], v[162:165], v[178:181], v[60:63]
	s_waitcnt lgkmcnt(3)
	v_mfma_f32_16x16x32_bf16 v[72:75], v[158:161], v[222:225], v[72:75]
	v_mfma_f32_16x16x32_bf16 v[76:79], v[162:165], v[222:225], v[76:79]
	s_waitcnt lgkmcnt(2)
	s_mov_b32 m0, s50
	v_mfma_f32_16x16x32_bf16 v[48:51], v[214:217], v[166:169], v[48:51]
	global_load_lds_dwordx4 v146, s[68:69]
	s_waitcnt lgkmcnt(1)
	v_mfma_f32_16x16x32_bf16 v[174:177], v[218:221], v[166:169], v[174:177]
	ds_read_b128 v[166:169], v28
	v_mfma_f32_16x16x32_bf16 v[64:67], v[214:217], v[178:181], v[64:67]
	v_mfma_f32_16x16x32_bf16 v[170:173], v[218:221], v[178:181], v[170:173]
	ds_read_b128 v[178:181], v29
	v_mfma_f32_16x16x32_bf16 v[80:83], v[214:217], v[222:225], v[80:83]
	v_mfma_f32_16x16x32_bf16 v[32:35], v[218:221], v[222:225], v[32:35]
	ds_read_b128 v[222:225], v30
	s_waitcnt lgkmcnt(3)
	v_mfma_f32_16x16x32_bf16 v[88:91], v[158:161], v[226:229], v[88:91]
	v_mfma_f32_16x16x32_bf16 v[92:95], v[162:165], v[226:229], v[92:95]
	v_mfma_f32_16x16x32_bf16 v[96:99], v[214:217], v[226:229], v[96:99]
	v_mfma_f32_16x16x32_bf16 v[36:39], v[218:221], v[226:229], v[36:39]
	ds_read_b128 v[226:229], v31
	s_waitcnt lgkmcnt(3)
	v_mfma_f32_16x16x32_bf16 v[104:107], v[158:161], v[166:169], v[104:107]
	v_mfma_f32_16x16x32_bf16 v[108:111], v[162:165], v[166:169], v[108:111]
	v_mfma_f32_16x16x32_bf16 v[112:115], v[214:217], v[166:169], v[112:115]
	v_mfma_f32_16x16x32_bf16 v[52:55], v[218:221], v[166:169], v[52:55]
	s_waitcnt lgkmcnt(2)
	v_mfma_f32_16x16x32_bf16 v[116:119], v[158:161], v[178:181], v[116:119]
	v_mfma_f32_16x16x32_bf16 v[120:123], v[162:165], v[178:181], v[120:123]
	v_mfma_f32_16x16x32_bf16 v[124:127], v[214:217], v[178:181], v[124:127]
	v_mfma_f32_16x16x32_bf16 v[68:71], v[218:221], v[178:181], v[68:71]
	s_waitcnt lgkmcnt(1)
	v_mfma_f32_16x16x32_bf16 v[128:131], v[158:161], v[222:225], v[128:131]
	v_mfma_f32_16x16x32_bf16 v[132:135], v[162:165], v[222:225], v[132:135]
	v_mfma_f32_16x16x32_bf16 v[136:139], v[214:217], v[222:225], v[136:139]
	v_mfma_f32_16x16x32_bf16 v[84:87], v[218:221], v[222:225], v[84:87]
	s_waitcnt lgkmcnt(0)
	v_mfma_f32_16x16x32_bf16 v[100:103], v[158:161], v[226:229], v[100:103]
	v_mfma_f32_16x16x32_bf16 v[140:143], v[162:165], v[226:229], v[140:143]
	v_mfma_f32_16x16x32_bf16 v[150:153], v[214:217], v[226:229], v[150:153]
	v_mfma_f32_16x16x32_bf16 v[154:157], v[218:221], v[226:229], v[154:157]
	s_add_u32 s64, s0, 0xa80
	s_addc_u32 s65, s1, 0
	s_add_u32 s68, s14, 0xa80
	s_waitcnt vmcnt(0)
	s_barrier
	s_addc_u32 s69, s15, 0
	ds_read_b128 v[158:161], v7 offset:32768
	ds_read_b128 v[162:165], v6
	ds_read_b128 v[166:169], v7 offset:34816
	ds_read_b128 v[178:181], v6 offset:2048
	ds_read_b128 v[214:217], v7 offset:36864
	ds_read_b128 v[218:221], v7 offset:38912
	ds_read_b128 v[222:225], v6 offset:4096
	ds_read_b128 v[226:229], v6 offset:6144
	s_waitcnt lgkmcnt(6)
	v_mfma_f32_16x16x32_bf16 v[40:43], v[158:161], v[162:165], v[40:43]
	s_waitcnt lgkmcnt(5)
	v_mfma_f32_16x16x32_bf16 v[44:47], v[166:169], v[162:165], v[44:47]
	s_waitcnt lgkmcnt(4)
	v_mfma_f32_16x16x32_bf16 v[56:59], v[158:161], v[178:181], v[56:59]
	s_mov_b32 m0, s52
	v_mfma_f32_16x16x32_bf16 v[60:63], v[166:169], v[178:181], v[60:63]
	global_load_lds_dwordx4 v0, s[64:65]
	s_waitcnt lgkmcnt(3)
	v_mfma_f32_16x16x32_bf16 v[48:51], v[214:217], v[162:165], v[48:51]
	v_mfma_f32_16x16x32_bf16 v[64:67], v[214:217], v[178:181], v[64:67]
	s_waitcnt lgkmcnt(2)
	v_mfma_f32_16x16x32_bf16 v[174:177], v[218:221], v[162:165], v[174:177]
	ds_read_b128 v[162:165], v6 offset:8192
	v_mfma_f32_16x16x32_bf16 v[170:173], v[218:221], v[178:181], v[170:173]
	ds_read_b128 v[178:181], v6 offset:10240
	s_waitcnt lgkmcnt(3)
	s_mov_b32 m0, s51
	v_mfma_f32_16x16x32_bf16 v[72:75], v[158:161], v[222:225], v[72:75]
	global_load_lds_dwordx4 v0, s[68:69]
	v_mfma_f32_16x16x32_bf16 v[76:79], v[166:169], v[222:225], v[76:79]
	v_mfma_f32_16x16x32_bf16 v[80:83], v[214:217], v[222:225], v[80:83]
	v_mfma_f32_16x16x32_bf16 v[32:35], v[218:221], v[222:225], v[32:35]
	ds_read_b128 v[222:225], v6 offset:12288
	s_waitcnt lgkmcnt(3)
	v_mfma_f32_16x16x32_bf16 v[88:91], v[158:161], v[226:229], v[88:91]
	s_mov_b32 m0, s53
	v_mfma_f32_16x16x32_bf16 v[92:95], v[166:169], v[226:229], v[92:95]
	global_load_lds_dwordx4 v2, s[64:65]
	v_mfma_f32_16x16x32_bf16 v[96:99], v[214:217], v[226:229], v[96:99]
	v_mfma_f32_16x16x32_bf16 v[36:39], v[218:221], v[226:229], v[36:39]
	ds_read_b128 v[226:229], v6 offset:14336
	s_waitcnt lgkmcnt(3)
	v_mfma_f32_16x16x32_bf16 v[104:107], v[158:161], v[162:165], v[104:107]
	s_waitcnt lgkmcnt(2)
	v_mfma_f32_16x16x32_bf16 v[116:119], v[158:161], v[178:181], v[116:119]
	s_waitcnt lgkmcnt(1)
	s_mov_b32 m0, s54
	v_mfma_f32_16x16x32_bf16 v[128:131], v[158:161], v[222:225], v[128:131]
	global_load_lds_dwordx4 v2, s[68:69]
	s_waitcnt lgkmcnt(0)
	v_mfma_f32_16x16x32_bf16 v[100:103], v[158:161], v[226:229], v[100:103]
	ds_read_b128 v[158:161], v7 offset:33792
	v_mfma_f32_16x16x32_bf16 v[108:111], v[166:169], v[162:165], v[108:111]
	v_mfma_f32_16x16x32_bf16 v[120:123], v[166:169], v[178:181], v[120:123]
	v_mfma_f32_16x16x32_bf16 v[132:135], v[166:169], v[222:225], v[132:135]
	s_mov_b32 m0, s55
	v_mfma_f32_16x16x32_bf16 v[140:143], v[166:169], v[226:229], v[140:143]
	global_load_lds_dwordx4 v4, s[64:65]
	ds_read_b128 v[166:169], v6 offset:1024
	v_mfma_f32_16x16x32_bf16 v[112:115], v[214:217], v[162:165], v[112:115]
	v_mfma_f32_16x16x32_bf16 v[52:55], v[218:221], v[162:165], v[52:55]
	ds_read_b128 v[162:165], v7 offset:35840
	v_mfma_f32_16x16x32_bf16 v[124:127], v[214:217], v[178:181], v[124:127]
	v_mfma_f32_16x16x32_bf16 v[68:71], v[218:221], v[178:181], v[68:71]
	ds_read_b128 v[178:181], v6 offset:3072
	s_mov_b32 m0, s58
	v_mfma_f32_16x16x32_bf16 v[136:139], v[214:217], v[222:225], v[136:139]
	global_load_lds_dwordx4 v4, s[68:69]
	v_mfma_f32_16x16x32_bf16 v[84:87], v[218:221], v[222:225], v[84:87]
	ds_read_b128 v[222:225], v6 offset:5120
	v_mfma_f32_16x16x32_bf16 v[150:153], v[214:217], v[226:229], v[150:153]
	ds_read_b128 v[214:217], v7 offset:37888
	v_mfma_f32_16x16x32_bf16 v[154:157], v[218:221], v[226:229], v[154:157]
	ds_read_b128 v[218:221], v7 offset:39936
	ds_read_b128 v[226:229], v6 offset:7168
	s_waitcnt lgkmcnt(6)
	v_mfma_f32_16x16x32_bf16 v[40:43], v[158:161], v[166:169], v[40:43]
	s_waitcnt lgkmcnt(5)
	s_mov_b32 m0, s62
	v_mfma_f32_16x16x32_bf16 v[44:47], v[162:165], v[166:169], v[44:47]
	global_load_lds_dwordx4 v146, s[64:65]
	s_waitcnt lgkmcnt(4)
	v_mfma_f32_16x16x32_bf16 v[56:59], v[158:161], v[178:181], v[56:59]
	v_mfma_f32_16x16x32_bf16 v[60:63], v[162:165], v[178:181], v[60:63]
	s_waitcnt lgkmcnt(3)
	v_mfma_f32_16x16x32_bf16 v[72:75], v[158:161], v[222:225], v[72:75]
	v_mfma_f32_16x16x32_bf16 v[76:79], v[162:165], v[222:225], v[76:79]
	s_waitcnt lgkmcnt(2)
	s_mov_b32 m0, s63
	v_mfma_f32_16x16x32_bf16 v[48:51], v[214:217], v[166:169], v[48:51]
	global_load_lds_dwordx4 v146, s[68:69]
	s_waitcnt lgkmcnt(1)
	v_mfma_f32_16x16x32_bf16 v[174:177], v[218:221], v[166:169], v[174:177]
	ds_read_b128 v[166:169], v6 offset:9216
	v_mfma_f32_16x16x32_bf16 v[64:67], v[214:217], v[178:181], v[64:67]
	v_mfma_f32_16x16x32_bf16 v[170:173], v[218:221], v[178:181], v[170:173]
	ds_read_b128 v[178:181], v6 offset:11264
	v_mfma_f32_16x16x32_bf16 v[80:83], v[214:217], v[222:225], v[80:83]
	v_mfma_f32_16x16x32_bf16 v[32:35], v[218:221], v[222:225], v[32:35]
	ds_read_b128 v[222:225], v6 offset:13312
	s_waitcnt lgkmcnt(3)
	v_mfma_f32_16x16x32_bf16 v[88:91], v[158:161], v[226:229], v[88:91]
	v_mfma_f32_16x16x32_bf16 v[92:95], v[162:165], v[226:229], v[92:95]
	v_mfma_f32_16x16x32_bf16 v[96:99], v[214:217], v[226:229], v[96:99]
	v_mfma_f32_16x16x32_bf16 v[36:39], v[218:221], v[226:229], v[36:39]
	ds_read_b128 v[226:229], v6 offset:15360
	s_waitcnt lgkmcnt(3)
	v_mfma_f32_16x16x32_bf16 v[104:107], v[158:161], v[166:169], v[104:107]
	v_mfma_f32_16x16x32_bf16 v[108:111], v[162:165], v[166:169], v[108:111]
	v_mfma_f32_16x16x32_bf16 v[112:115], v[214:217], v[166:169], v[112:115]
	v_mfma_f32_16x16x32_bf16 v[52:55], v[218:221], v[166:169], v[52:55]
	s_waitcnt lgkmcnt(2)
	v_mfma_f32_16x16x32_bf16 v[116:119], v[158:161], v[178:181], v[116:119]
	v_mfma_f32_16x16x32_bf16 v[120:123], v[162:165], v[178:181], v[120:123]
	v_mfma_f32_16x16x32_bf16 v[124:127], v[214:217], v[178:181], v[124:127]
	v_mfma_f32_16x16x32_bf16 v[68:71], v[218:221], v[178:181], v[68:71]
	s_waitcnt lgkmcnt(1)
	v_mfma_f32_16x16x32_bf16 v[128:131], v[158:161], v[222:225], v[128:131]
	v_mfma_f32_16x16x32_bf16 v[132:135], v[162:165], v[222:225], v[132:135]
	v_mfma_f32_16x16x32_bf16 v[136:139], v[214:217], v[222:225], v[136:139]
	v_mfma_f32_16x16x32_bf16 v[84:87], v[218:221], v[222:225], v[84:87]
	s_waitcnt lgkmcnt(0)
	v_mfma_f32_16x16x32_bf16 v[100:103], v[158:161], v[226:229], v[100:103]
	v_mfma_f32_16x16x32_bf16 v[140:143], v[162:165], v[226:229], v[140:143]
	v_mfma_f32_16x16x32_bf16 v[150:153], v[214:217], v[226:229], v[150:153]
	v_mfma_f32_16x16x32_bf16 v[154:157], v[218:221], v[226:229], v[154:157]
	s_add_u32 s64, s0, 0xb00
	s_addc_u32 s65, s1, 0
	s_add_u32 s68, s14, 0xb00
	s_waitcnt vmcnt(0)
	s_barrier
	s_addc_u32 s69, s15, 0
	ds_read_b128 v[158:161], v8
	ds_read_b128 v[162:165], v12
	ds_read_b128 v[166:169], v9
	ds_read_b128 v[178:181], v13
	ds_read_b128 v[214:217], v11
	ds_read_b128 v[218:221], v10
	ds_read_b128 v[222:225], v14
	ds_read_b128 v[226:229], v15
	s_waitcnt lgkmcnt(6)
	v_mfma_f32_16x16x32_bf16 v[40:43], v[158:161], v[162:165], v[40:43]
	s_waitcnt lgkmcnt(5)
	v_mfma_f32_16x16x32_bf16 v[44:47], v[166:169], v[162:165], v[44:47]
	s_waitcnt lgkmcnt(4)
	v_mfma_f32_16x16x32_bf16 v[56:59], v[158:161], v[178:181], v[56:59]
	s_mov_b32 m0, s42
	v_mfma_f32_16x16x32_bf16 v[60:63], v[166:169], v[178:181], v[60:63]
	global_load_lds_dwordx4 v0, s[64:65]
	s_waitcnt lgkmcnt(3)
	v_mfma_f32_16x16x32_bf16 v[48:51], v[214:217], v[162:165], v[48:51]
	v_mfma_f32_16x16x32_bf16 v[64:67], v[214:217], v[178:181], v[64:67]
	s_waitcnt lgkmcnt(2)
	v_mfma_f32_16x16x32_bf16 v[174:177], v[218:221], v[162:165], v[174:177]
	ds_read_b128 v[162:165], v16
	v_mfma_f32_16x16x32_bf16 v[170:173], v[218:221], v[178:181], v[170:173]
	ds_read_b128 v[178:181], v17
	s_waitcnt lgkmcnt(3)
	s_mov_b32 m0, s43
	v_mfma_f32_16x16x32_bf16 v[72:75], v[158:161], v[222:225], v[72:75]
	global_load_lds_dwordx4 v0, s[68:69]
	v_mfma_f32_16x16x32_bf16 v[76:79], v[166:169], v[222:225], v[76:79]
	v_mfma_f32_16x16x32_bf16 v[80:83], v[214:217], v[222:225], v[80:83]
	v_mfma_f32_16x16x32_bf16 v[32:35], v[218:221], v[222:225], v[32:35]
	ds_read_b128 v[222:225], v18
	s_waitcnt lgkmcnt(3)
	v_mfma_f32_16x16x32_bf16 v[88:91], v[158:161], v[226:229], v[88:91]
	s_mov_b32 m0, s44
	v_mfma_f32_16x16x32_bf16 v[92:95], v[166:169], v[226:229], v[92:95]
	global_load_lds_dwordx4 v2, s[64:65]
	v_mfma_f32_16x16x32_bf16 v[96:99], v[214:217], v[226:229], v[96:99]
	v_mfma_f32_16x16x32_bf16 v[36:39], v[218:221], v[226:229], v[36:39]
	ds_read_b128 v[226:229], v19
	s_waitcnt lgkmcnt(3)
	v_mfma_f32_16x16x32_bf16 v[104:107], v[158:161], v[162:165], v[104:107]
	s_waitcnt lgkmcnt(2)
	v_mfma_f32_16x16x32_bf16 v[116:119], v[158:161], v[178:181], v[116:119]
	s_waitcnt lgkmcnt(1)
	s_mov_b32 m0, s45
	v_mfma_f32_16x16x32_bf16 v[128:131], v[158:161], v[222:225], v[128:131]
	global_load_lds_dwordx4 v2, s[68:69]
	s_waitcnt lgkmcnt(0)
	v_mfma_f32_16x16x32_bf16 v[100:103], v[158:161], v[226:229], v[100:103]
	ds_read_b128 v[158:161], v20
	v_mfma_f32_16x16x32_bf16 v[108:111], v[166:169], v[162:165], v[108:111]
	v_mfma_f32_16x16x32_bf16 v[120:123], v[166:169], v[178:181], v[120:123]
	v_mfma_f32_16x16x32_bf16 v[132:135], v[166:169], v[222:225], v[132:135]
	s_mov_b32 m0, s46
	v_mfma_f32_16x16x32_bf16 v[140:143], v[166:169], v[226:229], v[140:143]
	global_load_lds_dwordx4 v4, s[64:65]
	ds_read_b128 v[166:169], v24
	v_mfma_f32_16x16x32_bf16 v[112:115], v[214:217], v[162:165], v[112:115]
	v_mfma_f32_16x16x32_bf16 v[52:55], v[218:221], v[162:165], v[52:55]
	ds_read_b128 v[162:165], v21
	v_mfma_f32_16x16x32_bf16 v[124:127], v[214:217], v[178:181], v[124:127]
	v_mfma_f32_16x16x32_bf16 v[68:71], v[218:221], v[178:181], v[68:71]
	ds_read_b128 v[178:181], v25
	s_mov_b32 m0, s47
	v_mfma_f32_16x16x32_bf16 v[136:139], v[214:217], v[222:225], v[136:139]
	global_load_lds_dwordx4 v4, s[68:69]
	v_mfma_f32_16x16x32_bf16 v[84:87], v[218:221], v[222:225], v[84:87]
	ds_read_b128 v[222:225], v26
	v_mfma_f32_16x16x32_bf16 v[150:153], v[214:217], v[226:229], v[150:153]
	ds_read_b128 v[214:217], v23
	v_mfma_f32_16x16x32_bf16 v[154:157], v[218:221], v[226:229], v[154:157]
	ds_read_b128 v[218:221], v22
	ds_read_b128 v[226:229], v27
	s_waitcnt lgkmcnt(6)
	v_mfma_f32_16x16x32_bf16 v[40:43], v[158:161], v[166:169], v[40:43]
	s_waitcnt lgkmcnt(5)
	s_mov_b32 m0, s49
	v_mfma_f32_16x16x32_bf16 v[44:47], v[162:165], v[166:169], v[44:47]
	global_load_lds_dwordx4 v146, s[64:65]
	s_waitcnt lgkmcnt(4)
	v_mfma_f32_16x16x32_bf16 v[56:59], v[158:161], v[178:181], v[56:59]
	v_mfma_f32_16x16x32_bf16 v[60:63], v[162:165], v[178:181], v[60:63]
	s_waitcnt lgkmcnt(3)
	v_mfma_f32_16x16x32_bf16 v[72:75], v[158:161], v[222:225], v[72:75]
	v_mfma_f32_16x16x32_bf16 v[76:79], v[162:165], v[222:225], v[76:79]
	s_waitcnt lgkmcnt(2)
	s_mov_b32 m0, s50
	v_mfma_f32_16x16x32_bf16 v[48:51], v[214:217], v[166:169], v[48:51]
	global_load_lds_dwordx4 v146, s[68:69]
	s_waitcnt lgkmcnt(1)
	v_mfma_f32_16x16x32_bf16 v[174:177], v[218:221], v[166:169], v[174:177]
	ds_read_b128 v[166:169], v28
	v_mfma_f32_16x16x32_bf16 v[64:67], v[214:217], v[178:181], v[64:67]
	v_mfma_f32_16x16x32_bf16 v[170:173], v[218:221], v[178:181], v[170:173]
	ds_read_b128 v[178:181], v29
	v_mfma_f32_16x16x32_bf16 v[80:83], v[214:217], v[222:225], v[80:83]
	v_mfma_f32_16x16x32_bf16 v[32:35], v[218:221], v[222:225], v[32:35]
	ds_read_b128 v[222:225], v30
	s_waitcnt lgkmcnt(3)
	v_mfma_f32_16x16x32_bf16 v[88:91], v[158:161], v[226:229], v[88:91]
	v_mfma_f32_16x16x32_bf16 v[92:95], v[162:165], v[226:229], v[92:95]
	v_mfma_f32_16x16x32_bf16 v[96:99], v[214:217], v[226:229], v[96:99]
	v_mfma_f32_16x16x32_bf16 v[36:39], v[218:221], v[226:229], v[36:39]
	ds_read_b128 v[226:229], v31
	s_waitcnt lgkmcnt(3)
	v_mfma_f32_16x16x32_bf16 v[104:107], v[158:161], v[166:169], v[104:107]
	v_mfma_f32_16x16x32_bf16 v[108:111], v[162:165], v[166:169], v[108:111]
	v_mfma_f32_16x16x32_bf16 v[112:115], v[214:217], v[166:169], v[112:115]
	v_mfma_f32_16x16x32_bf16 v[52:55], v[218:221], v[166:169], v[52:55]
	s_waitcnt lgkmcnt(2)
	v_mfma_f32_16x16x32_bf16 v[116:119], v[158:161], v[178:181], v[116:119]
	v_mfma_f32_16x16x32_bf16 v[120:123], v[162:165], v[178:181], v[120:123]
	v_mfma_f32_16x16x32_bf16 v[124:127], v[214:217], v[178:181], v[124:127]
	v_mfma_f32_16x16x32_bf16 v[68:71], v[218:221], v[178:181], v[68:71]
	s_waitcnt lgkmcnt(1)
	v_mfma_f32_16x16x32_bf16 v[128:131], v[158:161], v[222:225], v[128:131]
	v_mfma_f32_16x16x32_bf16 v[132:135], v[162:165], v[222:225], v[132:135]
	v_mfma_f32_16x16x32_bf16 v[136:139], v[214:217], v[222:225], v[136:139]
	v_mfma_f32_16x16x32_bf16 v[84:87], v[218:221], v[222:225], v[84:87]
	s_waitcnt lgkmcnt(0)
	v_mfma_f32_16x16x32_bf16 v[100:103], v[158:161], v[226:229], v[100:103]
	v_mfma_f32_16x16x32_bf16 v[140:143], v[162:165], v[226:229], v[140:143]
	v_mfma_f32_16x16x32_bf16 v[150:153], v[214:217], v[226:229], v[150:153]
	v_mfma_f32_16x16x32_bf16 v[154:157], v[218:221], v[226:229], v[154:157]
	s_add_u32 s64, s0, 0xb80
	s_addc_u32 s65, s1, 0
	s_add_u32 s68, s14, 0xb80
	s_waitcnt vmcnt(0)
	s_barrier
	s_addc_u32 s69, s15, 0
	ds_read_b128 v[158:161], v7 offset:32768
	ds_read_b128 v[162:165], v6
	ds_read_b128 v[166:169], v7 offset:34816
	ds_read_b128 v[178:181], v6 offset:2048
	ds_read_b128 v[214:217], v7 offset:36864
	ds_read_b128 v[218:221], v7 offset:38912
	ds_read_b128 v[222:225], v6 offset:4096
	ds_read_b128 v[226:229], v6 offset:6144
	s_waitcnt lgkmcnt(6)
	v_mfma_f32_16x16x32_bf16 v[40:43], v[158:161], v[162:165], v[40:43]
	s_waitcnt lgkmcnt(5)
	v_mfma_f32_16x16x32_bf16 v[44:47], v[166:169], v[162:165], v[44:47]
	s_waitcnt lgkmcnt(4)
	v_mfma_f32_16x16x32_bf16 v[56:59], v[158:161], v[178:181], v[56:59]
	s_mov_b32 m0, s52
	v_mfma_f32_16x16x32_bf16 v[60:63], v[166:169], v[178:181], v[60:63]
	global_load_lds_dwordx4 v0, s[64:65]
	s_waitcnt lgkmcnt(3)
	v_mfma_f32_16x16x32_bf16 v[48:51], v[214:217], v[162:165], v[48:51]
	v_mfma_f32_16x16x32_bf16 v[64:67], v[214:217], v[178:181], v[64:67]
	s_waitcnt lgkmcnt(2)
	v_mfma_f32_16x16x32_bf16 v[174:177], v[218:221], v[162:165], v[174:177]
	ds_read_b128 v[162:165], v6 offset:8192
	v_mfma_f32_16x16x32_bf16 v[170:173], v[218:221], v[178:181], v[170:173]
	ds_read_b128 v[178:181], v6 offset:10240
	s_waitcnt lgkmcnt(3)
	s_mov_b32 m0, s51
	v_mfma_f32_16x16x32_bf16 v[72:75], v[158:161], v[222:225], v[72:75]
	global_load_lds_dwordx4 v0, s[68:69]
	v_mfma_f32_16x16x32_bf16 v[76:79], v[166:169], v[222:225], v[76:79]
	v_mfma_f32_16x16x32_bf16 v[80:83], v[214:217], v[222:225], v[80:83]
	v_mfma_f32_16x16x32_bf16 v[32:35], v[218:221], v[222:225], v[32:35]
	ds_read_b128 v[222:225], v6 offset:12288
	s_waitcnt lgkmcnt(3)
	v_mfma_f32_16x16x32_bf16 v[88:91], v[158:161], v[226:229], v[88:91]
	s_mov_b32 m0, s53
	v_mfma_f32_16x16x32_bf16 v[92:95], v[166:169], v[226:229], v[92:95]
	global_load_lds_dwordx4 v2, s[64:65]
	v_mfma_f32_16x16x32_bf16 v[96:99], v[214:217], v[226:229], v[96:99]
	v_mfma_f32_16x16x32_bf16 v[36:39], v[218:221], v[226:229], v[36:39]
	ds_read_b128 v[226:229], v6 offset:14336
	s_waitcnt lgkmcnt(3)
	v_mfma_f32_16x16x32_bf16 v[104:107], v[158:161], v[162:165], v[104:107]
	s_waitcnt lgkmcnt(2)
	v_mfma_f32_16x16x32_bf16 v[116:119], v[158:161], v[178:181], v[116:119]
	s_waitcnt lgkmcnt(1)
	s_mov_b32 m0, s54
	v_mfma_f32_16x16x32_bf16 v[128:131], v[158:161], v[222:225], v[128:131]
	global_load_lds_dwordx4 v2, s[68:69]
	s_waitcnt lgkmcnt(0)
	v_mfma_f32_16x16x32_bf16 v[100:103], v[158:161], v[226:229], v[100:103]
	ds_read_b128 v[158:161], v7 offset:33792
	v_mfma_f32_16x16x32_bf16 v[108:111], v[166:169], v[162:165], v[108:111]
	v_mfma_f32_16x16x32_bf16 v[120:123], v[166:169], v[178:181], v[120:123]
	v_mfma_f32_16x16x32_bf16 v[132:135], v[166:169], v[222:225], v[132:135]
	s_mov_b32 m0, s55
	v_mfma_f32_16x16x32_bf16 v[140:143], v[166:169], v[226:229], v[140:143]
	global_load_lds_dwordx4 v4, s[64:65]
	ds_read_b128 v[166:169], v6 offset:1024
	v_mfma_f32_16x16x32_bf16 v[112:115], v[214:217], v[162:165], v[112:115]
	v_mfma_f32_16x16x32_bf16 v[52:55], v[218:221], v[162:165], v[52:55]
	ds_read_b128 v[162:165], v7 offset:35840
	v_mfma_f32_16x16x32_bf16 v[124:127], v[214:217], v[178:181], v[124:127]
	v_mfma_f32_16x16x32_bf16 v[68:71], v[218:221], v[178:181], v[68:71]
	ds_read_b128 v[178:181], v6 offset:3072
	s_mov_b32 m0, s58
	v_mfma_f32_16x16x32_bf16 v[136:139], v[214:217], v[222:225], v[136:139]
	global_load_lds_dwordx4 v4, s[68:69]
	v_mfma_f32_16x16x32_bf16 v[84:87], v[218:221], v[222:225], v[84:87]
	ds_read_b128 v[222:225], v6 offset:5120
	v_mfma_f32_16x16x32_bf16 v[150:153], v[214:217], v[226:229], v[150:153]
	ds_read_b128 v[214:217], v7 offset:37888
	v_mfma_f32_16x16x32_bf16 v[154:157], v[218:221], v[226:229], v[154:157]
	ds_read_b128 v[218:221], v7 offset:39936
	ds_read_b128 v[226:229], v6 offset:7168
	s_waitcnt lgkmcnt(6)
	v_mfma_f32_16x16x32_bf16 v[40:43], v[158:161], v[166:169], v[40:43]
	s_waitcnt lgkmcnt(5)
	s_mov_b32 m0, s62
	v_mfma_f32_16x16x32_bf16 v[44:47], v[162:165], v[166:169], v[44:47]
	global_load_lds_dwordx4 v146, s[64:65]
	s_waitcnt lgkmcnt(4)
	v_mfma_f32_16x16x32_bf16 v[56:59], v[158:161], v[178:181], v[56:59]
	v_mfma_f32_16x16x32_bf16 v[60:63], v[162:165], v[178:181], v[60:63]
	s_waitcnt lgkmcnt(3)
	v_mfma_f32_16x16x32_bf16 v[72:75], v[158:161], v[222:225], v[72:75]
	v_mfma_f32_16x16x32_bf16 v[76:79], v[162:165], v[222:225], v[76:79]
	s_waitcnt lgkmcnt(2)
	s_mov_b32 m0, s63
	v_mfma_f32_16x16x32_bf16 v[48:51], v[214:217], v[166:169], v[48:51]
	global_load_lds_dwordx4 v146, s[68:69]
	s_waitcnt lgkmcnt(1)
	v_mfma_f32_16x16x32_bf16 v[174:177], v[218:221], v[166:169], v[174:177]
	ds_read_b128 v[166:169], v6 offset:9216
	v_mfma_f32_16x16x32_bf16 v[64:67], v[214:217], v[178:181], v[64:67]
	v_mfma_f32_16x16x32_bf16 v[170:173], v[218:221], v[178:181], v[170:173]
	ds_read_b128 v[178:181], v6 offset:11264
	v_mfma_f32_16x16x32_bf16 v[80:83], v[214:217], v[222:225], v[80:83]
	v_mfma_f32_16x16x32_bf16 v[32:35], v[218:221], v[222:225], v[32:35]
	ds_read_b128 v[222:225], v6 offset:13312
	s_waitcnt lgkmcnt(3)
	v_mfma_f32_16x16x32_bf16 v[88:91], v[158:161], v[226:229], v[88:91]
	v_mfma_f32_16x16x32_bf16 v[92:95], v[162:165], v[226:229], v[92:95]
	v_mfma_f32_16x16x32_bf16 v[96:99], v[214:217], v[226:229], v[96:99]
	v_mfma_f32_16x16x32_bf16 v[36:39], v[218:221], v[226:229], v[36:39]
	ds_read_b128 v[226:229], v6 offset:15360
	s_waitcnt lgkmcnt(3)
	v_mfma_f32_16x16x32_bf16 v[104:107], v[158:161], v[166:169], v[104:107]
	v_mfma_f32_16x16x32_bf16 v[108:111], v[162:165], v[166:169], v[108:111]
	v_mfma_f32_16x16x32_bf16 v[112:115], v[214:217], v[166:169], v[112:115]
	v_mfma_f32_16x16x32_bf16 v[52:55], v[218:221], v[166:169], v[52:55]
	s_waitcnt lgkmcnt(2)
	v_mfma_f32_16x16x32_bf16 v[116:119], v[158:161], v[178:181], v[116:119]
	v_mfma_f32_16x16x32_bf16 v[120:123], v[162:165], v[178:181], v[120:123]
	v_mfma_f32_16x16x32_bf16 v[124:127], v[214:217], v[178:181], v[124:127]
	v_mfma_f32_16x16x32_bf16 v[68:71], v[218:221], v[178:181], v[68:71]
	s_waitcnt lgkmcnt(1)
	v_mfma_f32_16x16x32_bf16 v[128:131], v[158:161], v[222:225], v[128:131]
	v_mfma_f32_16x16x32_bf16 v[132:135], v[162:165], v[222:225], v[132:135]
	v_mfma_f32_16x16x32_bf16 v[136:139], v[214:217], v[222:225], v[136:139]
	v_mfma_f32_16x16x32_bf16 v[84:87], v[218:221], v[222:225], v[84:87]
	s_waitcnt lgkmcnt(0)
	v_mfma_f32_16x16x32_bf16 v[100:103], v[158:161], v[226:229], v[100:103]
	v_mfma_f32_16x16x32_bf16 v[140:143], v[162:165], v[226:229], v[140:143]
	v_mfma_f32_16x16x32_bf16 v[150:153], v[214:217], v[226:229], v[150:153]
	v_mfma_f32_16x16x32_bf16 v[154:157], v[218:221], v[226:229], v[154:157]
	s_add_u32 s64, s0, 0xc00
	s_addc_u32 s65, s1, 0
	s_add_u32 s68, s14, 0xc00
	s_waitcnt vmcnt(0)
	s_barrier
	s_addc_u32 s69, s15, 0
	ds_read_b128 v[158:161], v8
	ds_read_b128 v[162:165], v12
	ds_read_b128 v[166:169], v9
	ds_read_b128 v[178:181], v13
	ds_read_b128 v[214:217], v11
	ds_read_b128 v[218:221], v10
	ds_read_b128 v[222:225], v14
	ds_read_b128 v[226:229], v15
	s_waitcnt lgkmcnt(6)
	v_mfma_f32_16x16x32_bf16 v[40:43], v[158:161], v[162:165], v[40:43]
	s_waitcnt lgkmcnt(5)
	v_mfma_f32_16x16x32_bf16 v[44:47], v[166:169], v[162:165], v[44:47]
	s_waitcnt lgkmcnt(4)
	v_mfma_f32_16x16x32_bf16 v[56:59], v[158:161], v[178:181], v[56:59]
	s_mov_b32 m0, s42
	v_mfma_f32_16x16x32_bf16 v[60:63], v[166:169], v[178:181], v[60:63]
	global_load_lds_dwordx4 v0, s[64:65]
	s_waitcnt lgkmcnt(3)
	v_mfma_f32_16x16x32_bf16 v[48:51], v[214:217], v[162:165], v[48:51]
	v_mfma_f32_16x16x32_bf16 v[64:67], v[214:217], v[178:181], v[64:67]
	s_waitcnt lgkmcnt(2)
	v_mfma_f32_16x16x32_bf16 v[174:177], v[218:221], v[162:165], v[174:177]
	ds_read_b128 v[162:165], v16
	v_mfma_f32_16x16x32_bf16 v[170:173], v[218:221], v[178:181], v[170:173]
	ds_read_b128 v[178:181], v17
	s_waitcnt lgkmcnt(3)
	s_mov_b32 m0, s43
	v_mfma_f32_16x16x32_bf16 v[72:75], v[158:161], v[222:225], v[72:75]
	global_load_lds_dwordx4 v0, s[68:69]
	v_mfma_f32_16x16x32_bf16 v[76:79], v[166:169], v[222:225], v[76:79]
	v_mfma_f32_16x16x32_bf16 v[80:83], v[214:217], v[222:225], v[80:83]
	v_mfma_f32_16x16x32_bf16 v[32:35], v[218:221], v[222:225], v[32:35]
	ds_read_b128 v[222:225], v18
	s_waitcnt lgkmcnt(3)
	v_mfma_f32_16x16x32_bf16 v[88:91], v[158:161], v[226:229], v[88:91]
	s_mov_b32 m0, s44
	v_mfma_f32_16x16x32_bf16 v[92:95], v[166:169], v[226:229], v[92:95]
	global_load_lds_dwordx4 v2, s[64:65]
	v_mfma_f32_16x16x32_bf16 v[96:99], v[214:217], v[226:229], v[96:99]
	v_mfma_f32_16x16x32_bf16 v[36:39], v[218:221], v[226:229], v[36:39]
	ds_read_b128 v[226:229], v19
	s_waitcnt lgkmcnt(3)
	v_mfma_f32_16x16x32_bf16 v[104:107], v[158:161], v[162:165], v[104:107]
	s_waitcnt lgkmcnt(2)
	v_mfma_f32_16x16x32_bf16 v[116:119], v[158:161], v[178:181], v[116:119]
	s_waitcnt lgkmcnt(1)
	s_mov_b32 m0, s45
	v_mfma_f32_16x16x32_bf16 v[128:131], v[158:161], v[222:225], v[128:131]
	global_load_lds_dwordx4 v2, s[68:69]
	s_waitcnt lgkmcnt(0)
	v_mfma_f32_16x16x32_bf16 v[100:103], v[158:161], v[226:229], v[100:103]
	ds_read_b128 v[158:161], v20
	v_mfma_f32_16x16x32_bf16 v[108:111], v[166:169], v[162:165], v[108:111]
	v_mfma_f32_16x16x32_bf16 v[120:123], v[166:169], v[178:181], v[120:123]
	v_mfma_f32_16x16x32_bf16 v[132:135], v[166:169], v[222:225], v[132:135]
	s_mov_b32 m0, s46
	v_mfma_f32_16x16x32_bf16 v[140:143], v[166:169], v[226:229], v[140:143]
	global_load_lds_dwordx4 v4, s[64:65]
	ds_read_b128 v[166:169], v24
	v_mfma_f32_16x16x32_bf16 v[112:115], v[214:217], v[162:165], v[112:115]
	v_mfma_f32_16x16x32_bf16 v[52:55], v[218:221], v[162:165], v[52:55]
	ds_read_b128 v[162:165], v21
	v_mfma_f32_16x16x32_bf16 v[124:127], v[214:217], v[178:181], v[124:127]
	v_mfma_f32_16x16x32_bf16 v[68:71], v[218:221], v[178:181], v[68:71]
	ds_read_b128 v[178:181], v25
	s_mov_b32 m0, s47
	v_mfma_f32_16x16x32_bf16 v[136:139], v[214:217], v[222:225], v[136:139]
	global_load_lds_dwordx4 v4, s[68:69]
	v_mfma_f32_16x16x32_bf16 v[84:87], v[218:221], v[222:225], v[84:87]
	ds_read_b128 v[222:225], v26
	v_mfma_f32_16x16x32_bf16 v[150:153], v[214:217], v[226:229], v[150:153]
	ds_read_b128 v[214:217], v23
	v_mfma_f32_16x16x32_bf16 v[154:157], v[218:221], v[226:229], v[154:157]
	ds_read_b128 v[218:221], v22
	ds_read_b128 v[226:229], v27
	s_waitcnt lgkmcnt(6)
	v_mfma_f32_16x16x32_bf16 v[40:43], v[158:161], v[166:169], v[40:43]
	s_waitcnt lgkmcnt(5)
	s_mov_b32 m0, s49
	v_mfma_f32_16x16x32_bf16 v[44:47], v[162:165], v[166:169], v[44:47]
	global_load_lds_dwordx4 v146, s[64:65]
	s_waitcnt lgkmcnt(4)
	v_mfma_f32_16x16x32_bf16 v[56:59], v[158:161], v[178:181], v[56:59]
	v_mfma_f32_16x16x32_bf16 v[60:63], v[162:165], v[178:181], v[60:63]
	s_waitcnt lgkmcnt(3)
	v_mfma_f32_16x16x32_bf16 v[72:75], v[158:161], v[222:225], v[72:75]
	v_mfma_f32_16x16x32_bf16 v[76:79], v[162:165], v[222:225], v[76:79]
	s_waitcnt lgkmcnt(2)
	s_mov_b32 m0, s50
	v_mfma_f32_16x16x32_bf16 v[48:51], v[214:217], v[166:169], v[48:51]
	global_load_lds_dwordx4 v146, s[68:69]
	s_waitcnt lgkmcnt(1)
	v_mfma_f32_16x16x32_bf16 v[174:177], v[218:221], v[166:169], v[174:177]
	ds_read_b128 v[166:169], v28
	v_mfma_f32_16x16x32_bf16 v[64:67], v[214:217], v[178:181], v[64:67]
	v_mfma_f32_16x16x32_bf16 v[170:173], v[218:221], v[178:181], v[170:173]
	ds_read_b128 v[178:181], v29
	v_mfma_f32_16x16x32_bf16 v[80:83], v[214:217], v[222:225], v[80:83]
	v_mfma_f32_16x16x32_bf16 v[32:35], v[218:221], v[222:225], v[32:35]
	ds_read_b128 v[222:225], v30
	s_waitcnt lgkmcnt(3)
	v_mfma_f32_16x16x32_bf16 v[88:91], v[158:161], v[226:229], v[88:91]
	v_mfma_f32_16x16x32_bf16 v[92:95], v[162:165], v[226:229], v[92:95]
	v_mfma_f32_16x16x32_bf16 v[96:99], v[214:217], v[226:229], v[96:99]
	v_mfma_f32_16x16x32_bf16 v[36:39], v[218:221], v[226:229], v[36:39]
	ds_read_b128 v[226:229], v31
	s_waitcnt lgkmcnt(3)
	v_mfma_f32_16x16x32_bf16 v[104:107], v[158:161], v[166:169], v[104:107]
	v_mfma_f32_16x16x32_bf16 v[108:111], v[162:165], v[166:169], v[108:111]
	v_mfma_f32_16x16x32_bf16 v[112:115], v[214:217], v[166:169], v[112:115]
	v_mfma_f32_16x16x32_bf16 v[52:55], v[218:221], v[166:169], v[52:55]
	s_waitcnt lgkmcnt(2)
	v_mfma_f32_16x16x32_bf16 v[116:119], v[158:161], v[178:181], v[116:119]
	v_mfma_f32_16x16x32_bf16 v[120:123], v[162:165], v[178:181], v[120:123]
	v_mfma_f32_16x16x32_bf16 v[124:127], v[214:217], v[178:181], v[124:127]
	v_mfma_f32_16x16x32_bf16 v[68:71], v[218:221], v[178:181], v[68:71]
	s_waitcnt lgkmcnt(1)
	v_mfma_f32_16x16x32_bf16 v[128:131], v[158:161], v[222:225], v[128:131]
	v_mfma_f32_16x16x32_bf16 v[132:135], v[162:165], v[222:225], v[132:135]
	v_mfma_f32_16x16x32_bf16 v[136:139], v[214:217], v[222:225], v[136:139]
	v_mfma_f32_16x16x32_bf16 v[84:87], v[218:221], v[222:225], v[84:87]
	s_waitcnt lgkmcnt(0)
	v_mfma_f32_16x16x32_bf16 v[100:103], v[158:161], v[226:229], v[100:103]
	v_mfma_f32_16x16x32_bf16 v[140:143], v[162:165], v[226:229], v[140:143]
	v_mfma_f32_16x16x32_bf16 v[150:153], v[214:217], v[226:229], v[150:153]
	v_mfma_f32_16x16x32_bf16 v[154:157], v[218:221], v[226:229], v[154:157]
	s_add_u32 s64, s0, 0xc80
	s_addc_u32 s65, s1, 0
	s_add_u32 s68, s14, 0xc80
	s_waitcnt vmcnt(0)
	s_barrier
	s_addc_u32 s69, s15, 0
	ds_read_b128 v[158:161], v7 offset:32768
	ds_read_b128 v[162:165], v6
	ds_read_b128 v[166:169], v7 offset:34816
	ds_read_b128 v[178:181], v6 offset:2048
	ds_read_b128 v[214:217], v7 offset:36864
	ds_read_b128 v[218:221], v7 offset:38912
	ds_read_b128 v[222:225], v6 offset:4096
	ds_read_b128 v[226:229], v6 offset:6144
	s_waitcnt lgkmcnt(6)
	v_mfma_f32_16x16x32_bf16 v[40:43], v[158:161], v[162:165], v[40:43]
	s_waitcnt lgkmcnt(5)
	v_mfma_f32_16x16x32_bf16 v[44:47], v[166:169], v[162:165], v[44:47]
	s_waitcnt lgkmcnt(4)
	v_mfma_f32_16x16x32_bf16 v[56:59], v[158:161], v[178:181], v[56:59]
	s_mov_b32 m0, s52
	v_mfma_f32_16x16x32_bf16 v[60:63], v[166:169], v[178:181], v[60:63]
	global_load_lds_dwordx4 v0, s[64:65]
	s_waitcnt lgkmcnt(3)
	v_mfma_f32_16x16x32_bf16 v[48:51], v[214:217], v[162:165], v[48:51]
	v_mfma_f32_16x16x32_bf16 v[64:67], v[214:217], v[178:181], v[64:67]
	s_waitcnt lgkmcnt(2)
	v_mfma_f32_16x16x32_bf16 v[174:177], v[218:221], v[162:165], v[174:177]
	ds_read_b128 v[162:165], v6 offset:8192
	v_mfma_f32_16x16x32_bf16 v[170:173], v[218:221], v[178:181], v[170:173]
	ds_read_b128 v[178:181], v6 offset:10240
	s_waitcnt lgkmcnt(3)
	s_mov_b32 m0, s51
	v_mfma_f32_16x16x32_bf16 v[72:75], v[158:161], v[222:225], v[72:75]
	global_load_lds_dwordx4 v0, s[68:69]
	v_mfma_f32_16x16x32_bf16 v[76:79], v[166:169], v[222:225], v[76:79]
	v_mfma_f32_16x16x32_bf16 v[80:83], v[214:217], v[222:225], v[80:83]
	v_mfma_f32_16x16x32_bf16 v[32:35], v[218:221], v[222:225], v[32:35]
	ds_read_b128 v[222:225], v6 offset:12288
	s_waitcnt lgkmcnt(3)
	v_mfma_f32_16x16x32_bf16 v[88:91], v[158:161], v[226:229], v[88:91]
	s_mov_b32 m0, s53
	v_mfma_f32_16x16x32_bf16 v[92:95], v[166:169], v[226:229], v[92:95]
	global_load_lds_dwordx4 v2, s[64:65]
	v_mfma_f32_16x16x32_bf16 v[96:99], v[214:217], v[226:229], v[96:99]
	v_mfma_f32_16x16x32_bf16 v[36:39], v[218:221], v[226:229], v[36:39]
	ds_read_b128 v[226:229], v6 offset:14336
	s_waitcnt lgkmcnt(3)
	v_mfma_f32_16x16x32_bf16 v[104:107], v[158:161], v[162:165], v[104:107]
	s_waitcnt lgkmcnt(2)
	v_mfma_f32_16x16x32_bf16 v[116:119], v[158:161], v[178:181], v[116:119]
	s_waitcnt lgkmcnt(1)
	s_mov_b32 m0, s54
	v_mfma_f32_16x16x32_bf16 v[128:131], v[158:161], v[222:225], v[128:131]
	global_load_lds_dwordx4 v2, s[68:69]
	s_waitcnt lgkmcnt(0)
	v_mfma_f32_16x16x32_bf16 v[100:103], v[158:161], v[226:229], v[100:103]
	ds_read_b128 v[158:161], v7 offset:33792
	v_mfma_f32_16x16x32_bf16 v[108:111], v[166:169], v[162:165], v[108:111]
	v_mfma_f32_16x16x32_bf16 v[120:123], v[166:169], v[178:181], v[120:123]
	v_mfma_f32_16x16x32_bf16 v[132:135], v[166:169], v[222:225], v[132:135]
	s_mov_b32 m0, s55
	v_mfma_f32_16x16x32_bf16 v[140:143], v[166:169], v[226:229], v[140:143]
	global_load_lds_dwordx4 v4, s[64:65]
	ds_read_b128 v[166:169], v6 offset:1024
	v_mfma_f32_16x16x32_bf16 v[112:115], v[214:217], v[162:165], v[112:115]
	v_mfma_f32_16x16x32_bf16 v[52:55], v[218:221], v[162:165], v[52:55]
	ds_read_b128 v[162:165], v7 offset:35840
	v_mfma_f32_16x16x32_bf16 v[124:127], v[214:217], v[178:181], v[124:127]
	v_mfma_f32_16x16x32_bf16 v[68:71], v[218:221], v[178:181], v[68:71]
	ds_read_b128 v[178:181], v6 offset:3072
	s_mov_b32 m0, s58
	v_mfma_f32_16x16x32_bf16 v[136:139], v[214:217], v[222:225], v[136:139]
	global_load_lds_dwordx4 v4, s[68:69]
	v_mfma_f32_16x16x32_bf16 v[84:87], v[218:221], v[222:225], v[84:87]
	ds_read_b128 v[222:225], v6 offset:5120
	v_mfma_f32_16x16x32_bf16 v[150:153], v[214:217], v[226:229], v[150:153]
	ds_read_b128 v[214:217], v7 offset:37888
	v_mfma_f32_16x16x32_bf16 v[154:157], v[218:221], v[226:229], v[154:157]
	ds_read_b128 v[218:221], v7 offset:39936
	ds_read_b128 v[226:229], v6 offset:7168
	s_waitcnt lgkmcnt(6)
	v_mfma_f32_16x16x32_bf16 v[40:43], v[158:161], v[166:169], v[40:43]
	s_waitcnt lgkmcnt(5)
	s_mov_b32 m0, s62
	v_mfma_f32_16x16x32_bf16 v[44:47], v[162:165], v[166:169], v[44:47]
	global_load_lds_dwordx4 v146, s[64:65]
	s_waitcnt lgkmcnt(4)
	v_mfma_f32_16x16x32_bf16 v[56:59], v[158:161], v[178:181], v[56:59]
	v_mfma_f32_16x16x32_bf16 v[60:63], v[162:165], v[178:181], v[60:63]
	s_waitcnt lgkmcnt(3)
	v_mfma_f32_16x16x32_bf16 v[72:75], v[158:161], v[222:225], v[72:75]
	v_mfma_f32_16x16x32_bf16 v[76:79], v[162:165], v[222:225], v[76:79]
	s_waitcnt lgkmcnt(2)
	s_mov_b32 m0, s63
	v_mfma_f32_16x16x32_bf16 v[48:51], v[214:217], v[166:169], v[48:51]
	global_load_lds_dwordx4 v146, s[68:69]
	s_waitcnt lgkmcnt(1)
	v_mfma_f32_16x16x32_bf16 v[174:177], v[218:221], v[166:169], v[174:177]
	ds_read_b128 v[166:169], v6 offset:9216
	v_mfma_f32_16x16x32_bf16 v[64:67], v[214:217], v[178:181], v[64:67]
	v_mfma_f32_16x16x32_bf16 v[170:173], v[218:221], v[178:181], v[170:173]
	ds_read_b128 v[178:181], v6 offset:11264
	v_mfma_f32_16x16x32_bf16 v[80:83], v[214:217], v[222:225], v[80:83]
	v_mfma_f32_16x16x32_bf16 v[32:35], v[218:221], v[222:225], v[32:35]
	ds_read_b128 v[222:225], v6 offset:13312
	s_waitcnt lgkmcnt(3)
	v_mfma_f32_16x16x32_bf16 v[88:91], v[158:161], v[226:229], v[88:91]
	v_mfma_f32_16x16x32_bf16 v[92:95], v[162:165], v[226:229], v[92:95]
	v_mfma_f32_16x16x32_bf16 v[96:99], v[214:217], v[226:229], v[96:99]
	v_mfma_f32_16x16x32_bf16 v[36:39], v[218:221], v[226:229], v[36:39]
	ds_read_b128 v[226:229], v6 offset:15360
	s_waitcnt lgkmcnt(3)
	v_mfma_f32_16x16x32_bf16 v[104:107], v[158:161], v[166:169], v[104:107]
	v_mfma_f32_16x16x32_bf16 v[108:111], v[162:165], v[166:169], v[108:111]
	v_mfma_f32_16x16x32_bf16 v[112:115], v[214:217], v[166:169], v[112:115]
	v_mfma_f32_16x16x32_bf16 v[52:55], v[218:221], v[166:169], v[52:55]
	s_waitcnt lgkmcnt(2)
	v_mfma_f32_16x16x32_bf16 v[116:119], v[158:161], v[178:181], v[116:119]
	v_mfma_f32_16x16x32_bf16 v[120:123], v[162:165], v[178:181], v[120:123]
	v_mfma_f32_16x16x32_bf16 v[124:127], v[214:217], v[178:181], v[124:127]
	v_mfma_f32_16x16x32_bf16 v[68:71], v[218:221], v[178:181], v[68:71]
	s_waitcnt lgkmcnt(1)
	v_mfma_f32_16x16x32_bf16 v[128:131], v[158:161], v[222:225], v[128:131]
	v_mfma_f32_16x16x32_bf16 v[132:135], v[162:165], v[222:225], v[132:135]
	v_mfma_f32_16x16x32_bf16 v[136:139], v[214:217], v[222:225], v[136:139]
	v_mfma_f32_16x16x32_bf16 v[84:87], v[218:221], v[222:225], v[84:87]
	s_waitcnt lgkmcnt(0)
	v_mfma_f32_16x16x32_bf16 v[100:103], v[158:161], v[226:229], v[100:103]
	v_mfma_f32_16x16x32_bf16 v[140:143], v[162:165], v[226:229], v[140:143]
	v_mfma_f32_16x16x32_bf16 v[150:153], v[214:217], v[226:229], v[150:153]
	v_mfma_f32_16x16x32_bf16 v[154:157], v[218:221], v[226:229], v[154:157]
	s_add_u32 s64, s0, 0xd00
	s_addc_u32 s65, s1, 0
	s_add_u32 s68, s14, 0xd00
	s_waitcnt vmcnt(0)
	s_barrier
	s_addc_u32 s69, s15, 0
	ds_read_b128 v[158:161], v8
	ds_read_b128 v[162:165], v12
	ds_read_b128 v[166:169], v9
	ds_read_b128 v[178:181], v13
	ds_read_b128 v[214:217], v11
	ds_read_b128 v[218:221], v10
	ds_read_b128 v[222:225], v14
	ds_read_b128 v[226:229], v15
	s_waitcnt lgkmcnt(6)
	v_mfma_f32_16x16x32_bf16 v[40:43], v[158:161], v[162:165], v[40:43]
	s_waitcnt lgkmcnt(5)
	v_mfma_f32_16x16x32_bf16 v[44:47], v[166:169], v[162:165], v[44:47]
	s_waitcnt lgkmcnt(4)
	v_mfma_f32_16x16x32_bf16 v[56:59], v[158:161], v[178:181], v[56:59]
	s_mov_b32 m0, s42
	v_mfma_f32_16x16x32_bf16 v[60:63], v[166:169], v[178:181], v[60:63]
	global_load_lds_dwordx4 v0, s[64:65]
	s_waitcnt lgkmcnt(3)
	v_mfma_f32_16x16x32_bf16 v[48:51], v[214:217], v[162:165], v[48:51]
	v_mfma_f32_16x16x32_bf16 v[64:67], v[214:217], v[178:181], v[64:67]
	s_waitcnt lgkmcnt(2)
	v_mfma_f32_16x16x32_bf16 v[174:177], v[218:221], v[162:165], v[174:177]
	ds_read_b128 v[162:165], v16
	v_mfma_f32_16x16x32_bf16 v[170:173], v[218:221], v[178:181], v[170:173]
	ds_read_b128 v[178:181], v17
	s_waitcnt lgkmcnt(3)
	s_mov_b32 m0, s43
	v_mfma_f32_16x16x32_bf16 v[72:75], v[158:161], v[222:225], v[72:75]
	global_load_lds_dwordx4 v0, s[68:69]
	v_mfma_f32_16x16x32_bf16 v[76:79], v[166:169], v[222:225], v[76:79]
	v_mfma_f32_16x16x32_bf16 v[80:83], v[214:217], v[222:225], v[80:83]
	v_mfma_f32_16x16x32_bf16 v[32:35], v[218:221], v[222:225], v[32:35]
	ds_read_b128 v[222:225], v18
	s_waitcnt lgkmcnt(3)
	v_mfma_f32_16x16x32_bf16 v[88:91], v[158:161], v[226:229], v[88:91]
	s_mov_b32 m0, s44
	v_mfma_f32_16x16x32_bf16 v[92:95], v[166:169], v[226:229], v[92:95]
	global_load_lds_dwordx4 v2, s[64:65]
	v_mfma_f32_16x16x32_bf16 v[96:99], v[214:217], v[226:229], v[96:99]
	v_mfma_f32_16x16x32_bf16 v[36:39], v[218:221], v[226:229], v[36:39]
	ds_read_b128 v[226:229], v19
	s_waitcnt lgkmcnt(3)
	v_mfma_f32_16x16x32_bf16 v[104:107], v[158:161], v[162:165], v[104:107]
	s_waitcnt lgkmcnt(2)
	v_mfma_f32_16x16x32_bf16 v[116:119], v[158:161], v[178:181], v[116:119]
	s_waitcnt lgkmcnt(1)
	s_mov_b32 m0, s45
	v_mfma_f32_16x16x32_bf16 v[128:131], v[158:161], v[222:225], v[128:131]
	global_load_lds_dwordx4 v2, s[68:69]
	s_waitcnt lgkmcnt(0)
	v_mfma_f32_16x16x32_bf16 v[100:103], v[158:161], v[226:229], v[100:103]
	ds_read_b128 v[158:161], v20
	v_mfma_f32_16x16x32_bf16 v[108:111], v[166:169], v[162:165], v[108:111]
	v_mfma_f32_16x16x32_bf16 v[120:123], v[166:169], v[178:181], v[120:123]
	v_mfma_f32_16x16x32_bf16 v[132:135], v[166:169], v[222:225], v[132:135]
	s_mov_b32 m0, s46
	v_mfma_f32_16x16x32_bf16 v[140:143], v[166:169], v[226:229], v[140:143]
	global_load_lds_dwordx4 v4, s[64:65]
	ds_read_b128 v[166:169], v24
	v_mfma_f32_16x16x32_bf16 v[112:115], v[214:217], v[162:165], v[112:115]
	v_mfma_f32_16x16x32_bf16 v[52:55], v[218:221], v[162:165], v[52:55]
	ds_read_b128 v[162:165], v21
	v_mfma_f32_16x16x32_bf16 v[124:127], v[214:217], v[178:181], v[124:127]
	v_mfma_f32_16x16x32_bf16 v[68:71], v[218:221], v[178:181], v[68:71]
	ds_read_b128 v[178:181], v25
	s_mov_b32 m0, s47
	v_mfma_f32_16x16x32_bf16 v[136:139], v[214:217], v[222:225], v[136:139]
	global_load_lds_dwordx4 v4, s[68:69]
	v_mfma_f32_16x16x32_bf16 v[84:87], v[218:221], v[222:225], v[84:87]
	ds_read_b128 v[222:225], v26
	v_mfma_f32_16x16x32_bf16 v[150:153], v[214:217], v[226:229], v[150:153]
	ds_read_b128 v[214:217], v23
	v_mfma_f32_16x16x32_bf16 v[154:157], v[218:221], v[226:229], v[154:157]
	ds_read_b128 v[218:221], v22
	ds_read_b128 v[226:229], v27
	s_waitcnt lgkmcnt(6)
	v_mfma_f32_16x16x32_bf16 v[40:43], v[158:161], v[166:169], v[40:43]
	s_waitcnt lgkmcnt(5)
	s_mov_b32 m0, s49
	v_mfma_f32_16x16x32_bf16 v[44:47], v[162:165], v[166:169], v[44:47]
	global_load_lds_dwordx4 v146, s[64:65]
	s_waitcnt lgkmcnt(4)
	v_mfma_f32_16x16x32_bf16 v[56:59], v[158:161], v[178:181], v[56:59]
	v_mfma_f32_16x16x32_bf16 v[60:63], v[162:165], v[178:181], v[60:63]
	s_waitcnt lgkmcnt(3)
	v_mfma_f32_16x16x32_bf16 v[72:75], v[158:161], v[222:225], v[72:75]
	v_mfma_f32_16x16x32_bf16 v[76:79], v[162:165], v[222:225], v[76:79]
	s_waitcnt lgkmcnt(2)
	s_mov_b32 m0, s50
	v_mfma_f32_16x16x32_bf16 v[48:51], v[214:217], v[166:169], v[48:51]
	global_load_lds_dwordx4 v146, s[68:69]
	s_waitcnt lgkmcnt(1)
	v_mfma_f32_16x16x32_bf16 v[174:177], v[218:221], v[166:169], v[174:177]
	ds_read_b128 v[166:169], v28
	v_mfma_f32_16x16x32_bf16 v[64:67], v[214:217], v[178:181], v[64:67]
	v_mfma_f32_16x16x32_bf16 v[170:173], v[218:221], v[178:181], v[170:173]
	ds_read_b128 v[178:181], v29
	v_mfma_f32_16x16x32_bf16 v[80:83], v[214:217], v[222:225], v[80:83]
	v_mfma_f32_16x16x32_bf16 v[32:35], v[218:221], v[222:225], v[32:35]
	ds_read_b128 v[222:225], v30
	s_waitcnt lgkmcnt(3)
	v_mfma_f32_16x16x32_bf16 v[88:91], v[158:161], v[226:229], v[88:91]
	v_mfma_f32_16x16x32_bf16 v[92:95], v[162:165], v[226:229], v[92:95]
	v_mfma_f32_16x16x32_bf16 v[96:99], v[214:217], v[226:229], v[96:99]
	v_mfma_f32_16x16x32_bf16 v[36:39], v[218:221], v[226:229], v[36:39]
	ds_read_b128 v[226:229], v31
	s_waitcnt lgkmcnt(3)
	v_mfma_f32_16x16x32_bf16 v[104:107], v[158:161], v[166:169], v[104:107]
	v_mfma_f32_16x16x32_bf16 v[108:111], v[162:165], v[166:169], v[108:111]
	v_mfma_f32_16x16x32_bf16 v[112:115], v[214:217], v[166:169], v[112:115]
	v_mfma_f32_16x16x32_bf16 v[52:55], v[218:221], v[166:169], v[52:55]
	s_waitcnt lgkmcnt(2)
	v_mfma_f32_16x16x32_bf16 v[116:119], v[158:161], v[178:181], v[116:119]
	v_mfma_f32_16x16x32_bf16 v[120:123], v[162:165], v[178:181], v[120:123]
	v_mfma_f32_16x16x32_bf16 v[124:127], v[214:217], v[178:181], v[124:127]
	v_mfma_f32_16x16x32_bf16 v[68:71], v[218:221], v[178:181], v[68:71]
	s_waitcnt lgkmcnt(1)
	v_mfma_f32_16x16x32_bf16 v[128:131], v[158:161], v[222:225], v[128:131]
	v_mfma_f32_16x16x32_bf16 v[132:135], v[162:165], v[222:225], v[132:135]
	v_mfma_f32_16x16x32_bf16 v[136:139], v[214:217], v[222:225], v[136:139]
	v_mfma_f32_16x16x32_bf16 v[84:87], v[218:221], v[222:225], v[84:87]
	s_waitcnt lgkmcnt(0)
	v_mfma_f32_16x16x32_bf16 v[100:103], v[158:161], v[226:229], v[100:103]
	v_mfma_f32_16x16x32_bf16 v[140:143], v[162:165], v[226:229], v[140:143]
	v_mfma_f32_16x16x32_bf16 v[150:153], v[214:217], v[226:229], v[150:153]
	v_mfma_f32_16x16x32_bf16 v[154:157], v[218:221], v[226:229], v[154:157]
	s_add_u32 s64, s0, 0xd80
	s_addc_u32 s65, s1, 0
	s_add_u32 s68, s14, 0xd80
	s_waitcnt vmcnt(0)
	s_barrier
	s_addc_u32 s69, s15, 0
	ds_read_b128 v[158:161], v7 offset:32768
	ds_read_b128 v[162:165], v6
	ds_read_b128 v[166:169], v7 offset:34816
	ds_read_b128 v[178:181], v6 offset:2048
	ds_read_b128 v[214:217], v7 offset:36864
	ds_read_b128 v[218:221], v7 offset:38912
	ds_read_b128 v[222:225], v6 offset:4096
	ds_read_b128 v[226:229], v6 offset:6144
	s_waitcnt lgkmcnt(6)
	v_mfma_f32_16x16x32_bf16 v[40:43], v[158:161], v[162:165], v[40:43]
	s_waitcnt lgkmcnt(5)
	v_mfma_f32_16x16x32_bf16 v[44:47], v[166:169], v[162:165], v[44:47]
	s_waitcnt lgkmcnt(4)
	v_mfma_f32_16x16x32_bf16 v[56:59], v[158:161], v[178:181], v[56:59]
	s_mov_b32 m0, s52
	v_mfma_f32_16x16x32_bf16 v[60:63], v[166:169], v[178:181], v[60:63]
	global_load_lds_dwordx4 v0, s[64:65]
	s_waitcnt lgkmcnt(3)
	v_mfma_f32_16x16x32_bf16 v[48:51], v[214:217], v[162:165], v[48:51]
	v_mfma_f32_16x16x32_bf16 v[64:67], v[214:217], v[178:181], v[64:67]
	s_waitcnt lgkmcnt(2)
	v_mfma_f32_16x16x32_bf16 v[174:177], v[218:221], v[162:165], v[174:177]
	ds_read_b128 v[162:165], v6 offset:8192
	v_mfma_f32_16x16x32_bf16 v[170:173], v[218:221], v[178:181], v[170:173]
	ds_read_b128 v[178:181], v6 offset:10240
	s_waitcnt lgkmcnt(3)
	s_mov_b32 m0, s51
	v_mfma_f32_16x16x32_bf16 v[72:75], v[158:161], v[222:225], v[72:75]
	global_load_lds_dwordx4 v0, s[68:69]
	v_mfma_f32_16x16x32_bf16 v[76:79], v[166:169], v[222:225], v[76:79]
	v_mfma_f32_16x16x32_bf16 v[80:83], v[214:217], v[222:225], v[80:83]
	v_mfma_f32_16x16x32_bf16 v[32:35], v[218:221], v[222:225], v[32:35]
	ds_read_b128 v[222:225], v6 offset:12288
	s_waitcnt lgkmcnt(3)
	v_mfma_f32_16x16x32_bf16 v[88:91], v[158:161], v[226:229], v[88:91]
	s_mov_b32 m0, s53
	v_mfma_f32_16x16x32_bf16 v[92:95], v[166:169], v[226:229], v[92:95]
	global_load_lds_dwordx4 v2, s[64:65]
	v_mfma_f32_16x16x32_bf16 v[96:99], v[214:217], v[226:229], v[96:99]
	v_mfma_f32_16x16x32_bf16 v[36:39], v[218:221], v[226:229], v[36:39]
	ds_read_b128 v[226:229], v6 offset:14336
	s_waitcnt lgkmcnt(3)
	v_mfma_f32_16x16x32_bf16 v[104:107], v[158:161], v[162:165], v[104:107]
	s_waitcnt lgkmcnt(2)
	v_mfma_f32_16x16x32_bf16 v[116:119], v[158:161], v[178:181], v[116:119]
	s_waitcnt lgkmcnt(1)
	s_mov_b32 m0, s54
	v_mfma_f32_16x16x32_bf16 v[128:131], v[158:161], v[222:225], v[128:131]
	global_load_lds_dwordx4 v2, s[68:69]
	s_waitcnt lgkmcnt(0)
	v_mfma_f32_16x16x32_bf16 v[100:103], v[158:161], v[226:229], v[100:103]
	ds_read_b128 v[158:161], v7 offset:33792
	v_mfma_f32_16x16x32_bf16 v[108:111], v[166:169], v[162:165], v[108:111]
	v_mfma_f32_16x16x32_bf16 v[120:123], v[166:169], v[178:181], v[120:123]
	v_mfma_f32_16x16x32_bf16 v[132:135], v[166:169], v[222:225], v[132:135]
	s_mov_b32 m0, s55
	v_mfma_f32_16x16x32_bf16 v[140:143], v[166:169], v[226:229], v[140:143]
	global_load_lds_dwordx4 v4, s[64:65]
	ds_read_b128 v[166:169], v6 offset:1024
	v_mfma_f32_16x16x32_bf16 v[112:115], v[214:217], v[162:165], v[112:115]
	v_mfma_f32_16x16x32_bf16 v[52:55], v[218:221], v[162:165], v[52:55]
	ds_read_b128 v[162:165], v7 offset:35840
	v_mfma_f32_16x16x32_bf16 v[124:127], v[214:217], v[178:181], v[124:127]
	v_mfma_f32_16x16x32_bf16 v[68:71], v[218:221], v[178:181], v[68:71]
	ds_read_b128 v[178:181], v6 offset:3072
	s_mov_b32 m0, s58
	v_mfma_f32_16x16x32_bf16 v[136:139], v[214:217], v[222:225], v[136:139]
	global_load_lds_dwordx4 v4, s[68:69]
	v_mfma_f32_16x16x32_bf16 v[84:87], v[218:221], v[222:225], v[84:87]
	ds_read_b128 v[222:225], v6 offset:5120
	v_mfma_f32_16x16x32_bf16 v[150:153], v[214:217], v[226:229], v[150:153]
	ds_read_b128 v[214:217], v7 offset:37888
	v_mfma_f32_16x16x32_bf16 v[154:157], v[218:221], v[226:229], v[154:157]
	ds_read_b128 v[218:221], v7 offset:39936
	ds_read_b128 v[226:229], v6 offset:7168
	s_waitcnt lgkmcnt(6)
	v_mfma_f32_16x16x32_bf16 v[40:43], v[158:161], v[166:169], v[40:43]
	s_waitcnt lgkmcnt(5)
	s_mov_b32 m0, s62
	v_mfma_f32_16x16x32_bf16 v[44:47], v[162:165], v[166:169], v[44:47]
	global_load_lds_dwordx4 v146, s[64:65]
	s_waitcnt lgkmcnt(4)
	v_mfma_f32_16x16x32_bf16 v[56:59], v[158:161], v[178:181], v[56:59]
	v_mfma_f32_16x16x32_bf16 v[60:63], v[162:165], v[178:181], v[60:63]
	s_waitcnt lgkmcnt(3)
	v_mfma_f32_16x16x32_bf16 v[72:75], v[158:161], v[222:225], v[72:75]
	v_mfma_f32_16x16x32_bf16 v[76:79], v[162:165], v[222:225], v[76:79]
	s_waitcnt lgkmcnt(2)
	s_mov_b32 m0, s63
	v_mfma_f32_16x16x32_bf16 v[48:51], v[214:217], v[166:169], v[48:51]
	global_load_lds_dwordx4 v146, s[68:69]
	s_waitcnt lgkmcnt(1)
	v_mfma_f32_16x16x32_bf16 v[174:177], v[218:221], v[166:169], v[174:177]
	ds_read_b128 v[166:169], v6 offset:9216
	v_mfma_f32_16x16x32_bf16 v[64:67], v[214:217], v[178:181], v[64:67]
	v_mfma_f32_16x16x32_bf16 v[170:173], v[218:221], v[178:181], v[170:173]
	ds_read_b128 v[178:181], v6 offset:11264
	v_mfma_f32_16x16x32_bf16 v[80:83], v[214:217], v[222:225], v[80:83]
	v_mfma_f32_16x16x32_bf16 v[32:35], v[218:221], v[222:225], v[32:35]
	ds_read_b128 v[222:225], v6 offset:13312
	s_waitcnt lgkmcnt(3)
	v_mfma_f32_16x16x32_bf16 v[88:91], v[158:161], v[226:229], v[88:91]
	v_mfma_f32_16x16x32_bf16 v[92:95], v[162:165], v[226:229], v[92:95]
	v_mfma_f32_16x16x32_bf16 v[96:99], v[214:217], v[226:229], v[96:99]
	v_mfma_f32_16x16x32_bf16 v[36:39], v[218:221], v[226:229], v[36:39]
	ds_read_b128 v[226:229], v6 offset:15360
	s_waitcnt lgkmcnt(3)
	v_mfma_f32_16x16x32_bf16 v[104:107], v[158:161], v[166:169], v[104:107]
	v_mfma_f32_16x16x32_bf16 v[108:111], v[162:165], v[166:169], v[108:111]
	v_mfma_f32_16x16x32_bf16 v[112:115], v[214:217], v[166:169], v[112:115]
	v_mfma_f32_16x16x32_bf16 v[52:55], v[218:221], v[166:169], v[52:55]
	s_waitcnt lgkmcnt(2)
	v_mfma_f32_16x16x32_bf16 v[116:119], v[158:161], v[178:181], v[116:119]
	v_mfma_f32_16x16x32_bf16 v[120:123], v[162:165], v[178:181], v[120:123]
	v_mfma_f32_16x16x32_bf16 v[124:127], v[214:217], v[178:181], v[124:127]
	v_mfma_f32_16x16x32_bf16 v[68:71], v[218:221], v[178:181], v[68:71]
	s_waitcnt lgkmcnt(1)
	v_mfma_f32_16x16x32_bf16 v[128:131], v[158:161], v[222:225], v[128:131]
	v_mfma_f32_16x16x32_bf16 v[132:135], v[162:165], v[222:225], v[132:135]
	v_mfma_f32_16x16x32_bf16 v[136:139], v[214:217], v[222:225], v[136:139]
	v_mfma_f32_16x16x32_bf16 v[84:87], v[218:221], v[222:225], v[84:87]
	s_waitcnt lgkmcnt(0)
	v_mfma_f32_16x16x32_bf16 v[100:103], v[158:161], v[226:229], v[100:103]
	v_mfma_f32_16x16x32_bf16 v[140:143], v[162:165], v[226:229], v[140:143]
	v_mfma_f32_16x16x32_bf16 v[150:153], v[214:217], v[226:229], v[150:153]
	v_mfma_f32_16x16x32_bf16 v[154:157], v[218:221], v[226:229], v[154:157]
	s_add_u32 s64, s0, 0xe00
	s_addc_u32 s65, s1, 0
	s_add_u32 s68, s14, 0xe00
	s_waitcnt vmcnt(0)
	s_barrier
	s_addc_u32 s69, s15, 0
	ds_read_b128 v[158:161], v8
	ds_read_b128 v[162:165], v12
	ds_read_b128 v[166:169], v9
	ds_read_b128 v[178:181], v13
	ds_read_b128 v[214:217], v11
	ds_read_b128 v[218:221], v10
	ds_read_b128 v[222:225], v14
	ds_read_b128 v[226:229], v15
	s_waitcnt lgkmcnt(6)
	v_mfma_f32_16x16x32_bf16 v[40:43], v[158:161], v[162:165], v[40:43]
	s_waitcnt lgkmcnt(5)
	v_mfma_f32_16x16x32_bf16 v[44:47], v[166:169], v[162:165], v[44:47]
	s_waitcnt lgkmcnt(4)
	v_mfma_f32_16x16x32_bf16 v[56:59], v[158:161], v[178:181], v[56:59]
	s_mov_b32 m0, s42
	v_mfma_f32_16x16x32_bf16 v[60:63], v[166:169], v[178:181], v[60:63]
	global_load_lds_dwordx4 v0, s[64:65]
	s_waitcnt lgkmcnt(3)
	v_mfma_f32_16x16x32_bf16 v[48:51], v[214:217], v[162:165], v[48:51]
	v_mfma_f32_16x16x32_bf16 v[64:67], v[214:217], v[178:181], v[64:67]
	s_waitcnt lgkmcnt(2)
	v_mfma_f32_16x16x32_bf16 v[174:177], v[218:221], v[162:165], v[174:177]
	ds_read_b128 v[162:165], v16
	v_mfma_f32_16x16x32_bf16 v[170:173], v[218:221], v[178:181], v[170:173]
	ds_read_b128 v[178:181], v17
	s_waitcnt lgkmcnt(3)
	s_mov_b32 m0, s43
	v_mfma_f32_16x16x32_bf16 v[72:75], v[158:161], v[222:225], v[72:75]
	global_load_lds_dwordx4 v0, s[68:69]
	v_mfma_f32_16x16x32_bf16 v[76:79], v[166:169], v[222:225], v[76:79]
	v_mfma_f32_16x16x32_bf16 v[80:83], v[214:217], v[222:225], v[80:83]
	v_mfma_f32_16x16x32_bf16 v[32:35], v[218:221], v[222:225], v[32:35]
	ds_read_b128 v[222:225], v18
	s_waitcnt lgkmcnt(3)
	v_mfma_f32_16x16x32_bf16 v[88:91], v[158:161], v[226:229], v[88:91]
	s_mov_b32 m0, s44
	v_mfma_f32_16x16x32_bf16 v[92:95], v[166:169], v[226:229], v[92:95]
	global_load_lds_dwordx4 v2, s[64:65]
	v_mfma_f32_16x16x32_bf16 v[96:99], v[214:217], v[226:229], v[96:99]
	v_mfma_f32_16x16x32_bf16 v[36:39], v[218:221], v[226:229], v[36:39]
	ds_read_b128 v[226:229], v19
	s_waitcnt lgkmcnt(3)
	v_mfma_f32_16x16x32_bf16 v[104:107], v[158:161], v[162:165], v[104:107]
	s_waitcnt lgkmcnt(2)
	v_mfma_f32_16x16x32_bf16 v[116:119], v[158:161], v[178:181], v[116:119]
	s_waitcnt lgkmcnt(1)
	s_mov_b32 m0, s45
	v_mfma_f32_16x16x32_bf16 v[128:131], v[158:161], v[222:225], v[128:131]
	global_load_lds_dwordx4 v2, s[68:69]
	s_waitcnt lgkmcnt(0)
	v_mfma_f32_16x16x32_bf16 v[100:103], v[158:161], v[226:229], v[100:103]
	ds_read_b128 v[158:161], v20
	v_mfma_f32_16x16x32_bf16 v[108:111], v[166:169], v[162:165], v[108:111]
	v_mfma_f32_16x16x32_bf16 v[120:123], v[166:169], v[178:181], v[120:123]
	v_mfma_f32_16x16x32_bf16 v[132:135], v[166:169], v[222:225], v[132:135]
	s_mov_b32 m0, s46
	v_mfma_f32_16x16x32_bf16 v[140:143], v[166:169], v[226:229], v[140:143]
	global_load_lds_dwordx4 v4, s[64:65]
	ds_read_b128 v[166:169], v24
	v_mfma_f32_16x16x32_bf16 v[112:115], v[214:217], v[162:165], v[112:115]
	v_mfma_f32_16x16x32_bf16 v[52:55], v[218:221], v[162:165], v[52:55]
	ds_read_b128 v[162:165], v21
	v_mfma_f32_16x16x32_bf16 v[124:127], v[214:217], v[178:181], v[124:127]
	v_mfma_f32_16x16x32_bf16 v[68:71], v[218:221], v[178:181], v[68:71]
	ds_read_b128 v[178:181], v25
	s_mov_b32 m0, s47
	v_mfma_f32_16x16x32_bf16 v[136:139], v[214:217], v[222:225], v[136:139]
	global_load_lds_dwordx4 v4, s[68:69]
	v_mfma_f32_16x16x32_bf16 v[84:87], v[218:221], v[222:225], v[84:87]
	ds_read_b128 v[222:225], v26
	v_mfma_f32_16x16x32_bf16 v[150:153], v[214:217], v[226:229], v[150:153]
	ds_read_b128 v[214:217], v23
	v_mfma_f32_16x16x32_bf16 v[154:157], v[218:221], v[226:229], v[154:157]
	ds_read_b128 v[218:221], v22
	ds_read_b128 v[226:229], v27
	s_waitcnt lgkmcnt(6)
	v_mfma_f32_16x16x32_bf16 v[40:43], v[158:161], v[166:169], v[40:43]
	s_waitcnt lgkmcnt(5)
	s_mov_b32 m0, s49
	v_mfma_f32_16x16x32_bf16 v[44:47], v[162:165], v[166:169], v[44:47]
	global_load_lds_dwordx4 v146, s[64:65]
	s_waitcnt lgkmcnt(4)
	v_mfma_f32_16x16x32_bf16 v[56:59], v[158:161], v[178:181], v[56:59]
	v_mfma_f32_16x16x32_bf16 v[60:63], v[162:165], v[178:181], v[60:63]
	s_waitcnt lgkmcnt(3)
	v_mfma_f32_16x16x32_bf16 v[72:75], v[158:161], v[222:225], v[72:75]
	v_mfma_f32_16x16x32_bf16 v[76:79], v[162:165], v[222:225], v[76:79]
	s_waitcnt lgkmcnt(2)
	s_mov_b32 m0, s50
	v_mfma_f32_16x16x32_bf16 v[48:51], v[214:217], v[166:169], v[48:51]
	global_load_lds_dwordx4 v146, s[68:69]
	s_waitcnt lgkmcnt(1)
	v_mfma_f32_16x16x32_bf16 v[174:177], v[218:221], v[166:169], v[174:177]
	ds_read_b128 v[166:169], v28
	v_mfma_f32_16x16x32_bf16 v[64:67], v[214:217], v[178:181], v[64:67]
	v_mfma_f32_16x16x32_bf16 v[170:173], v[218:221], v[178:181], v[170:173]
	ds_read_b128 v[178:181], v29
	v_mfma_f32_16x16x32_bf16 v[80:83], v[214:217], v[222:225], v[80:83]
	v_mfma_f32_16x16x32_bf16 v[32:35], v[218:221], v[222:225], v[32:35]
	ds_read_b128 v[222:225], v30
	s_waitcnt lgkmcnt(3)
	v_mfma_f32_16x16x32_bf16 v[88:91], v[158:161], v[226:229], v[88:91]
	v_mfma_f32_16x16x32_bf16 v[92:95], v[162:165], v[226:229], v[92:95]
	v_mfma_f32_16x16x32_bf16 v[96:99], v[214:217], v[226:229], v[96:99]
	v_mfma_f32_16x16x32_bf16 v[36:39], v[218:221], v[226:229], v[36:39]
	ds_read_b128 v[226:229], v31
	s_waitcnt lgkmcnt(3)
	v_mfma_f32_16x16x32_bf16 v[104:107], v[158:161], v[166:169], v[104:107]
	v_mfma_f32_16x16x32_bf16 v[108:111], v[162:165], v[166:169], v[108:111]
	v_mfma_f32_16x16x32_bf16 v[112:115], v[214:217], v[166:169], v[112:115]
	v_mfma_f32_16x16x32_bf16 v[52:55], v[218:221], v[166:169], v[52:55]
	s_waitcnt lgkmcnt(2)
	v_mfma_f32_16x16x32_bf16 v[116:119], v[158:161], v[178:181], v[116:119]
	v_mfma_f32_16x16x32_bf16 v[120:123], v[162:165], v[178:181], v[120:123]
	v_mfma_f32_16x16x32_bf16 v[124:127], v[214:217], v[178:181], v[124:127]
	v_mfma_f32_16x16x32_bf16 v[68:71], v[218:221], v[178:181], v[68:71]
	s_waitcnt lgkmcnt(1)
	v_mfma_f32_16x16x32_bf16 v[128:131], v[158:161], v[222:225], v[128:131]
	v_mfma_f32_16x16x32_bf16 v[132:135], v[162:165], v[222:225], v[132:135]
	v_mfma_f32_16x16x32_bf16 v[136:139], v[214:217], v[222:225], v[136:139]
	v_mfma_f32_16x16x32_bf16 v[84:87], v[218:221], v[222:225], v[84:87]
	s_waitcnt lgkmcnt(0)
	v_mfma_f32_16x16x32_bf16 v[100:103], v[158:161], v[226:229], v[100:103]
	v_mfma_f32_16x16x32_bf16 v[140:143], v[162:165], v[226:229], v[140:143]
	v_mfma_f32_16x16x32_bf16 v[150:153], v[214:217], v[226:229], v[150:153]
	v_mfma_f32_16x16x32_bf16 v[154:157], v[218:221], v[226:229], v[154:157]
	s_add_u32 s64, s0, 0xe80
	s_addc_u32 s65, s1, 0
	s_add_u32 s68, s14, 0xe80
	s_waitcnt vmcnt(0)
	s_barrier
	s_addc_u32 s69, s15, 0
	ds_read_b128 v[158:161], v7 offset:32768
	ds_read_b128 v[162:165], v6
	ds_read_b128 v[166:169], v7 offset:34816
	ds_read_b128 v[178:181], v6 offset:2048
	ds_read_b128 v[214:217], v7 offset:36864
	ds_read_b128 v[218:221], v7 offset:38912
	ds_read_b128 v[222:225], v6 offset:4096
	ds_read_b128 v[226:229], v6 offset:6144
	s_waitcnt lgkmcnt(6)
	v_mfma_f32_16x16x32_bf16 v[40:43], v[158:161], v[162:165], v[40:43]
	s_waitcnt lgkmcnt(5)
	v_mfma_f32_16x16x32_bf16 v[44:47], v[166:169], v[162:165], v[44:47]
	s_waitcnt lgkmcnt(4)
	v_mfma_f32_16x16x32_bf16 v[56:59], v[158:161], v[178:181], v[56:59]
	s_mov_b32 m0, s52
	v_mfma_f32_16x16x32_bf16 v[60:63], v[166:169], v[178:181], v[60:63]
	global_load_lds_dwordx4 v0, s[64:65]
	s_waitcnt lgkmcnt(3)
	v_mfma_f32_16x16x32_bf16 v[48:51], v[214:217], v[162:165], v[48:51]
	v_mfma_f32_16x16x32_bf16 v[64:67], v[214:217], v[178:181], v[64:67]
	s_waitcnt lgkmcnt(2)
	v_mfma_f32_16x16x32_bf16 v[174:177], v[218:221], v[162:165], v[174:177]
	ds_read_b128 v[162:165], v6 offset:8192
	v_mfma_f32_16x16x32_bf16 v[170:173], v[218:221], v[178:181], v[170:173]
	ds_read_b128 v[178:181], v6 offset:10240
	s_waitcnt lgkmcnt(3)
	s_mov_b32 m0, s51
	v_mfma_f32_16x16x32_bf16 v[72:75], v[158:161], v[222:225], v[72:75]
	global_load_lds_dwordx4 v0, s[68:69]
	v_mfma_f32_16x16x32_bf16 v[76:79], v[166:169], v[222:225], v[76:79]
	v_mfma_f32_16x16x32_bf16 v[80:83], v[214:217], v[222:225], v[80:83]
	v_mfma_f32_16x16x32_bf16 v[32:35], v[218:221], v[222:225], v[32:35]
	ds_read_b128 v[222:225], v6 offset:12288
	s_waitcnt lgkmcnt(3)
	v_mfma_f32_16x16x32_bf16 v[88:91], v[158:161], v[226:229], v[88:91]
	s_mov_b32 m0, s53
	v_mfma_f32_16x16x32_bf16 v[92:95], v[166:169], v[226:229], v[92:95]
	global_load_lds_dwordx4 v2, s[64:65]
	v_mfma_f32_16x16x32_bf16 v[96:99], v[214:217], v[226:229], v[96:99]
	v_mfma_f32_16x16x32_bf16 v[36:39], v[218:221], v[226:229], v[36:39]
	ds_read_b128 v[226:229], v6 offset:14336
	s_waitcnt lgkmcnt(3)
	v_mfma_f32_16x16x32_bf16 v[104:107], v[158:161], v[162:165], v[104:107]
	s_waitcnt lgkmcnt(2)
	v_mfma_f32_16x16x32_bf16 v[116:119], v[158:161], v[178:181], v[116:119]
	s_waitcnt lgkmcnt(1)
	s_mov_b32 m0, s54
	v_mfma_f32_16x16x32_bf16 v[128:131], v[158:161], v[222:225], v[128:131]
	global_load_lds_dwordx4 v2, s[68:69]
	s_waitcnt lgkmcnt(0)
	v_mfma_f32_16x16x32_bf16 v[100:103], v[158:161], v[226:229], v[100:103]
	ds_read_b128 v[158:161], v7 offset:33792
	v_mfma_f32_16x16x32_bf16 v[108:111], v[166:169], v[162:165], v[108:111]
	v_mfma_f32_16x16x32_bf16 v[120:123], v[166:169], v[178:181], v[120:123]
	v_mfma_f32_16x16x32_bf16 v[132:135], v[166:169], v[222:225], v[132:135]
	s_mov_b32 m0, s55
	v_mfma_f32_16x16x32_bf16 v[140:143], v[166:169], v[226:229], v[140:143]
	global_load_lds_dwordx4 v4, s[64:65]
	ds_read_b128 v[166:169], v6 offset:1024
	v_mfma_f32_16x16x32_bf16 v[112:115], v[214:217], v[162:165], v[112:115]
	v_mfma_f32_16x16x32_bf16 v[52:55], v[218:221], v[162:165], v[52:55]
	ds_read_b128 v[162:165], v7 offset:35840
	v_mfma_f32_16x16x32_bf16 v[124:127], v[214:217], v[178:181], v[124:127]
	v_mfma_f32_16x16x32_bf16 v[68:71], v[218:221], v[178:181], v[68:71]
	ds_read_b128 v[178:181], v6 offset:3072
	s_mov_b32 m0, s58
	v_mfma_f32_16x16x32_bf16 v[136:139], v[214:217], v[222:225], v[136:139]
	global_load_lds_dwordx4 v4, s[68:69]
	v_mfma_f32_16x16x32_bf16 v[84:87], v[218:221], v[222:225], v[84:87]
	ds_read_b128 v[222:225], v6 offset:5120
	v_mfma_f32_16x16x32_bf16 v[150:153], v[214:217], v[226:229], v[150:153]
	ds_read_b128 v[214:217], v7 offset:37888
	v_mfma_f32_16x16x32_bf16 v[154:157], v[218:221], v[226:229], v[154:157]
	ds_read_b128 v[218:221], v7 offset:39936
	ds_read_b128 v[226:229], v6 offset:7168
	s_waitcnt lgkmcnt(6)
	v_mfma_f32_16x16x32_bf16 v[40:43], v[158:161], v[166:169], v[40:43]
	s_waitcnt lgkmcnt(5)
	s_mov_b32 m0, s62
	v_mfma_f32_16x16x32_bf16 v[44:47], v[162:165], v[166:169], v[44:47]
	global_load_lds_dwordx4 v146, s[64:65]
	s_waitcnt lgkmcnt(4)
	v_mfma_f32_16x16x32_bf16 v[56:59], v[158:161], v[178:181], v[56:59]
	v_mfma_f32_16x16x32_bf16 v[60:63], v[162:165], v[178:181], v[60:63]
	s_waitcnt lgkmcnt(3)
	v_mfma_f32_16x16x32_bf16 v[72:75], v[158:161], v[222:225], v[72:75]
	v_mfma_f32_16x16x32_bf16 v[76:79], v[162:165], v[222:225], v[76:79]
	s_waitcnt lgkmcnt(2)
	s_mov_b32 m0, s63
	v_mfma_f32_16x16x32_bf16 v[48:51], v[214:217], v[166:169], v[48:51]
	global_load_lds_dwordx4 v146, s[68:69]
	s_waitcnt lgkmcnt(1)
	v_mfma_f32_16x16x32_bf16 v[174:177], v[218:221], v[166:169], v[174:177]
	ds_read_b128 v[166:169], v6 offset:9216
	v_mfma_f32_16x16x32_bf16 v[64:67], v[214:217], v[178:181], v[64:67]
	v_mfma_f32_16x16x32_bf16 v[170:173], v[218:221], v[178:181], v[170:173]
	ds_read_b128 v[178:181], v6 offset:11264
	v_mfma_f32_16x16x32_bf16 v[80:83], v[214:217], v[222:225], v[80:83]
	v_mfma_f32_16x16x32_bf16 v[32:35], v[218:221], v[222:225], v[32:35]
	ds_read_b128 v[222:225], v6 offset:13312
	s_waitcnt lgkmcnt(3)
	v_mfma_f32_16x16x32_bf16 v[88:91], v[158:161], v[226:229], v[88:91]
	v_mfma_f32_16x16x32_bf16 v[92:95], v[162:165], v[226:229], v[92:95]
	v_mfma_f32_16x16x32_bf16 v[96:99], v[214:217], v[226:229], v[96:99]
	v_mfma_f32_16x16x32_bf16 v[36:39], v[218:221], v[226:229], v[36:39]
	ds_read_b128 v[226:229], v6 offset:15360
	s_waitcnt lgkmcnt(3)
	v_mfma_f32_16x16x32_bf16 v[104:107], v[158:161], v[166:169], v[104:107]
	v_mfma_f32_16x16x32_bf16 v[108:111], v[162:165], v[166:169], v[108:111]
	v_mfma_f32_16x16x32_bf16 v[112:115], v[214:217], v[166:169], v[112:115]
	v_mfma_f32_16x16x32_bf16 v[52:55], v[218:221], v[166:169], v[52:55]
	s_waitcnt lgkmcnt(2)
	v_mfma_f32_16x16x32_bf16 v[116:119], v[158:161], v[178:181], v[116:119]
	v_mfma_f32_16x16x32_bf16 v[120:123], v[162:165], v[178:181], v[120:123]
	v_mfma_f32_16x16x32_bf16 v[124:127], v[214:217], v[178:181], v[124:127]
	v_mfma_f32_16x16x32_bf16 v[68:71], v[218:221], v[178:181], v[68:71]
	s_waitcnt lgkmcnt(1)
	v_mfma_f32_16x16x32_bf16 v[128:131], v[158:161], v[222:225], v[128:131]
	v_mfma_f32_16x16x32_bf16 v[132:135], v[162:165], v[222:225], v[132:135]
	v_mfma_f32_16x16x32_bf16 v[136:139], v[214:217], v[222:225], v[136:139]
	v_mfma_f32_16x16x32_bf16 v[84:87], v[218:221], v[222:225], v[84:87]
	s_waitcnt lgkmcnt(0)
	v_mfma_f32_16x16x32_bf16 v[100:103], v[158:161], v[226:229], v[100:103]
	v_mfma_f32_16x16x32_bf16 v[140:143], v[162:165], v[226:229], v[140:143]
	v_mfma_f32_16x16x32_bf16 v[150:153], v[214:217], v[226:229], v[150:153]
	v_mfma_f32_16x16x32_bf16 v[154:157], v[218:221], v[226:229], v[154:157]
	s_add_u32 s64, s0, 0xf00
	s_addc_u32 s65, s1, 0
	s_add_u32 s68, s14, 0xf00
	s_waitcnt vmcnt(0)
	s_barrier
	s_addc_u32 s69, s15, 0
	ds_read_b128 v[158:161], v8
	ds_read_b128 v[162:165], v12
	ds_read_b128 v[166:169], v9
	ds_read_b128 v[178:181], v13
	ds_read_b128 v[214:217], v11
	ds_read_b128 v[218:221], v10
	ds_read_b128 v[222:225], v14
	ds_read_b128 v[226:229], v15
	s_waitcnt lgkmcnt(6)
	v_mfma_f32_16x16x32_bf16 v[40:43], v[158:161], v[162:165], v[40:43]
	s_waitcnt lgkmcnt(5)
	v_mfma_f32_16x16x32_bf16 v[44:47], v[166:169], v[162:165], v[44:47]
	s_waitcnt lgkmcnt(4)
	v_mfma_f32_16x16x32_bf16 v[56:59], v[158:161], v[178:181], v[56:59]
	s_mov_b32 m0, s42
	v_mfma_f32_16x16x32_bf16 v[60:63], v[166:169], v[178:181], v[60:63]
	global_load_lds_dwordx4 v0, s[64:65]
	s_waitcnt lgkmcnt(3)
	v_mfma_f32_16x16x32_bf16 v[48:51], v[214:217], v[162:165], v[48:51]
	v_mfma_f32_16x16x32_bf16 v[64:67], v[214:217], v[178:181], v[64:67]
	s_waitcnt lgkmcnt(2)
	v_mfma_f32_16x16x32_bf16 v[174:177], v[218:221], v[162:165], v[174:177]
	ds_read_b128 v[162:165], v16
	v_mfma_f32_16x16x32_bf16 v[170:173], v[218:221], v[178:181], v[170:173]
	ds_read_b128 v[178:181], v17
	s_waitcnt lgkmcnt(3)
	s_mov_b32 m0, s43
	v_mfma_f32_16x16x32_bf16 v[72:75], v[158:161], v[222:225], v[72:75]
	global_load_lds_dwordx4 v0, s[68:69]
	v_mfma_f32_16x16x32_bf16 v[76:79], v[166:169], v[222:225], v[76:79]
	v_mfma_f32_16x16x32_bf16 v[80:83], v[214:217], v[222:225], v[80:83]
	v_mfma_f32_16x16x32_bf16 v[32:35], v[218:221], v[222:225], v[32:35]
	ds_read_b128 v[222:225], v18
	s_waitcnt lgkmcnt(3)
	v_mfma_f32_16x16x32_bf16 v[88:91], v[158:161], v[226:229], v[88:91]
	s_mov_b32 m0, s44
	v_mfma_f32_16x16x32_bf16 v[92:95], v[166:169], v[226:229], v[92:95]
	global_load_lds_dwordx4 v2, s[64:65]
	v_mfma_f32_16x16x32_bf16 v[96:99], v[214:217], v[226:229], v[96:99]
	v_mfma_f32_16x16x32_bf16 v[36:39], v[218:221], v[226:229], v[36:39]
	ds_read_b128 v[226:229], v19
	s_waitcnt lgkmcnt(3)
	v_mfma_f32_16x16x32_bf16 v[104:107], v[158:161], v[162:165], v[104:107]
	s_waitcnt lgkmcnt(2)
	v_mfma_f32_16x16x32_bf16 v[116:119], v[158:161], v[178:181], v[116:119]
	s_waitcnt lgkmcnt(1)
	s_mov_b32 m0, s45
	v_mfma_f32_16x16x32_bf16 v[128:131], v[158:161], v[222:225], v[128:131]
	global_load_lds_dwordx4 v2, s[68:69]
	s_waitcnt lgkmcnt(0)
	v_mfma_f32_16x16x32_bf16 v[100:103], v[158:161], v[226:229], v[100:103]
	ds_read_b128 v[158:161], v20
	v_mfma_f32_16x16x32_bf16 v[108:111], v[166:169], v[162:165], v[108:111]
	v_mfma_f32_16x16x32_bf16 v[120:123], v[166:169], v[178:181], v[120:123]
	v_mfma_f32_16x16x32_bf16 v[132:135], v[166:169], v[222:225], v[132:135]
	s_mov_b32 m0, s46
	v_mfma_f32_16x16x32_bf16 v[140:143], v[166:169], v[226:229], v[140:143]
	global_load_lds_dwordx4 v4, s[64:65]
	ds_read_b128 v[166:169], v24
	v_mfma_f32_16x16x32_bf16 v[112:115], v[214:217], v[162:165], v[112:115]
	v_mfma_f32_16x16x32_bf16 v[52:55], v[218:221], v[162:165], v[52:55]
	ds_read_b128 v[162:165], v21
	v_mfma_f32_16x16x32_bf16 v[124:127], v[214:217], v[178:181], v[124:127]
	v_mfma_f32_16x16x32_bf16 v[68:71], v[218:221], v[178:181], v[68:71]
	ds_read_b128 v[178:181], v25
	s_mov_b32 m0, s47
	v_mfma_f32_16x16x32_bf16 v[136:139], v[214:217], v[222:225], v[136:139]
	global_load_lds_dwordx4 v4, s[68:69]
	v_mfma_f32_16x16x32_bf16 v[84:87], v[218:221], v[222:225], v[84:87]
	ds_read_b128 v[222:225], v26
	v_mfma_f32_16x16x32_bf16 v[150:153], v[214:217], v[226:229], v[150:153]
	ds_read_b128 v[214:217], v23
	v_mfma_f32_16x16x32_bf16 v[154:157], v[218:221], v[226:229], v[154:157]
	ds_read_b128 v[218:221], v22
	ds_read_b128 v[226:229], v27
	s_waitcnt lgkmcnt(6)
	v_mfma_f32_16x16x32_bf16 v[40:43], v[158:161], v[166:169], v[40:43]
	s_waitcnt lgkmcnt(5)
	s_mov_b32 m0, s49
	v_mfma_f32_16x16x32_bf16 v[44:47], v[162:165], v[166:169], v[44:47]
	global_load_lds_dwordx4 v146, s[64:65]
	s_waitcnt lgkmcnt(4)
	v_mfma_f32_16x16x32_bf16 v[56:59], v[158:161], v[178:181], v[56:59]
	v_mfma_f32_16x16x32_bf16 v[60:63], v[162:165], v[178:181], v[60:63]
	s_waitcnt lgkmcnt(3)
	v_mfma_f32_16x16x32_bf16 v[72:75], v[158:161], v[222:225], v[72:75]
	v_mfma_f32_16x16x32_bf16 v[76:79], v[162:165], v[222:225], v[76:79]
	s_waitcnt lgkmcnt(2)
	s_mov_b32 m0, s50
	v_mfma_f32_16x16x32_bf16 v[48:51], v[214:217], v[166:169], v[48:51]
	global_load_lds_dwordx4 v146, s[68:69]
	s_waitcnt lgkmcnt(1)
	v_mfma_f32_16x16x32_bf16 v[174:177], v[218:221], v[166:169], v[174:177]
	ds_read_b128 v[166:169], v28
	v_mfma_f32_16x16x32_bf16 v[64:67], v[214:217], v[178:181], v[64:67]
	v_mfma_f32_16x16x32_bf16 v[170:173], v[218:221], v[178:181], v[170:173]
	ds_read_b128 v[178:181], v29
	v_mfma_f32_16x16x32_bf16 v[80:83], v[214:217], v[222:225], v[80:83]
	v_mfma_f32_16x16x32_bf16 v[32:35], v[218:221], v[222:225], v[32:35]
	ds_read_b128 v[222:225], v30
	s_waitcnt lgkmcnt(3)
	v_mfma_f32_16x16x32_bf16 v[88:91], v[158:161], v[226:229], v[88:91]
	v_mfma_f32_16x16x32_bf16 v[92:95], v[162:165], v[226:229], v[92:95]
	v_mfma_f32_16x16x32_bf16 v[96:99], v[214:217], v[226:229], v[96:99]
	v_mfma_f32_16x16x32_bf16 v[36:39], v[218:221], v[226:229], v[36:39]
	ds_read_b128 v[226:229], v31
	s_waitcnt lgkmcnt(3)
	v_mfma_f32_16x16x32_bf16 v[104:107], v[158:161], v[166:169], v[104:107]
	v_mfma_f32_16x16x32_bf16 v[108:111], v[162:165], v[166:169], v[108:111]
	v_mfma_f32_16x16x32_bf16 v[112:115], v[214:217], v[166:169], v[112:115]
	v_mfma_f32_16x16x32_bf16 v[52:55], v[218:221], v[166:169], v[52:55]
	s_waitcnt lgkmcnt(2)
	v_mfma_f32_16x16x32_bf16 v[116:119], v[158:161], v[178:181], v[116:119]
	v_mfma_f32_16x16x32_bf16 v[120:123], v[162:165], v[178:181], v[120:123]
	v_mfma_f32_16x16x32_bf16 v[124:127], v[214:217], v[178:181], v[124:127]
	v_mfma_f32_16x16x32_bf16 v[68:71], v[218:221], v[178:181], v[68:71]
	s_waitcnt lgkmcnt(1)
	v_mfma_f32_16x16x32_bf16 v[128:131], v[158:161], v[222:225], v[128:131]
	v_mfma_f32_16x16x32_bf16 v[132:135], v[162:165], v[222:225], v[132:135]
	v_mfma_f32_16x16x32_bf16 v[136:139], v[214:217], v[222:225], v[136:139]
	v_mfma_f32_16x16x32_bf16 v[84:87], v[218:221], v[222:225], v[84:87]
	s_waitcnt lgkmcnt(0)
	v_mfma_f32_16x16x32_bf16 v[100:103], v[158:161], v[226:229], v[100:103]
	v_mfma_f32_16x16x32_bf16 v[140:143], v[162:165], v[226:229], v[140:143]
	v_mfma_f32_16x16x32_bf16 v[150:153], v[214:217], v[226:229], v[150:153]
	v_mfma_f32_16x16x32_bf16 v[154:157], v[218:221], v[226:229], v[154:157]
	s_add_u32 s64, s0, 0xf80
	s_addc_u32 s65, s1, 0
	s_add_u32 s68, s14, 0xf80
	s_waitcnt vmcnt(0)
	s_barrier
	s_addc_u32 s69, s15, 0
	ds_read_b128 v[158:161], v7 offset:32768
	ds_read_b128 v[162:165], v6
	ds_read_b128 v[166:169], v7 offset:34816
	ds_read_b128 v[178:181], v6 offset:2048
	ds_read_b128 v[214:217], v7 offset:36864
	ds_read_b128 v[218:221], v7 offset:38912
	ds_read_b128 v[222:225], v6 offset:4096
	ds_read_b128 v[226:229], v6 offset:6144
	s_waitcnt lgkmcnt(6)
	v_mfma_f32_16x16x32_bf16 v[40:43], v[158:161], v[162:165], v[40:43]
	s_waitcnt lgkmcnt(5)
	v_mfma_f32_16x16x32_bf16 v[44:47], v[166:169], v[162:165], v[44:47]
	s_waitcnt lgkmcnt(4)
	v_mfma_f32_16x16x32_bf16 v[56:59], v[158:161], v[178:181], v[56:59]
	s_mov_b32 m0, s52
	v_mfma_f32_16x16x32_bf16 v[60:63], v[166:169], v[178:181], v[60:63]
	global_load_lds_dwordx4 v0, s[64:65]
	s_waitcnt lgkmcnt(3)
	v_mfma_f32_16x16x32_bf16 v[48:51], v[214:217], v[162:165], v[48:51]
	v_mfma_f32_16x16x32_bf16 v[64:67], v[214:217], v[178:181], v[64:67]
	s_waitcnt lgkmcnt(2)
	v_mfma_f32_16x16x32_bf16 v[174:177], v[218:221], v[162:165], v[174:177]
	ds_read_b128 v[162:165], v6 offset:8192
	v_mfma_f32_16x16x32_bf16 v[170:173], v[218:221], v[178:181], v[170:173]
	ds_read_b128 v[178:181], v6 offset:10240
	s_waitcnt lgkmcnt(3)
	s_mov_b32 m0, s51
	v_mfma_f32_16x16x32_bf16 v[72:75], v[158:161], v[222:225], v[72:75]
	global_load_lds_dwordx4 v0, s[68:69]
	v_mfma_f32_16x16x32_bf16 v[76:79], v[166:169], v[222:225], v[76:79]
	v_mfma_f32_16x16x32_bf16 v[80:83], v[214:217], v[222:225], v[80:83]
	v_mfma_f32_16x16x32_bf16 v[32:35], v[218:221], v[222:225], v[32:35]
	ds_read_b128 v[222:225], v6 offset:12288
	s_waitcnt lgkmcnt(3)
	v_mfma_f32_16x16x32_bf16 v[88:91], v[158:161], v[226:229], v[88:91]
	s_mov_b32 m0, s53
	v_mfma_f32_16x16x32_bf16 v[92:95], v[166:169], v[226:229], v[92:95]
	global_load_lds_dwordx4 v2, s[64:65]
	v_mfma_f32_16x16x32_bf16 v[96:99], v[214:217], v[226:229], v[96:99]
	v_mfma_f32_16x16x32_bf16 v[36:39], v[218:221], v[226:229], v[36:39]
	ds_read_b128 v[226:229], v6 offset:14336
	s_waitcnt lgkmcnt(3)
	v_mfma_f32_16x16x32_bf16 v[104:107], v[158:161], v[162:165], v[104:107]
	s_waitcnt lgkmcnt(2)
	v_mfma_f32_16x16x32_bf16 v[116:119], v[158:161], v[178:181], v[116:119]
	s_waitcnt lgkmcnt(1)
	s_mov_b32 m0, s54
	v_mfma_f32_16x16x32_bf16 v[128:131], v[158:161], v[222:225], v[128:131]
	global_load_lds_dwordx4 v2, s[68:69]
	s_waitcnt lgkmcnt(0)
	v_mfma_f32_16x16x32_bf16 v[100:103], v[158:161], v[226:229], v[100:103]
	ds_read_b128 v[158:161], v7 offset:33792
	v_mfma_f32_16x16x32_bf16 v[108:111], v[166:169], v[162:165], v[108:111]
	v_mfma_f32_16x16x32_bf16 v[120:123], v[166:169], v[178:181], v[120:123]
	v_mfma_f32_16x16x32_bf16 v[132:135], v[166:169], v[222:225], v[132:135]
	s_mov_b32 m0, s55
	v_mfma_f32_16x16x32_bf16 v[140:143], v[166:169], v[226:229], v[140:143]
	global_load_lds_dwordx4 v4, s[64:65]
	ds_read_b128 v[166:169], v6 offset:1024
	v_mfma_f32_16x16x32_bf16 v[112:115], v[214:217], v[162:165], v[112:115]
	v_mfma_f32_16x16x32_bf16 v[52:55], v[218:221], v[162:165], v[52:55]
	ds_read_b128 v[162:165], v7 offset:35840
	v_mfma_f32_16x16x32_bf16 v[124:127], v[214:217], v[178:181], v[124:127]
	v_mfma_f32_16x16x32_bf16 v[68:71], v[218:221], v[178:181], v[68:71]
	ds_read_b128 v[178:181], v6 offset:3072
	s_mov_b32 m0, s58
	v_mfma_f32_16x16x32_bf16 v[136:139], v[214:217], v[222:225], v[136:139]
	global_load_lds_dwordx4 v4, s[68:69]
	v_mfma_f32_16x16x32_bf16 v[84:87], v[218:221], v[222:225], v[84:87]
	ds_read_b128 v[222:225], v6 offset:5120
	v_mfma_f32_16x16x32_bf16 v[150:153], v[214:217], v[226:229], v[150:153]
	ds_read_b128 v[214:217], v7 offset:37888
	v_mfma_f32_16x16x32_bf16 v[154:157], v[218:221], v[226:229], v[154:157]
	ds_read_b128 v[218:221], v7 offset:39936
	ds_read_b128 v[226:229], v6 offset:7168
	s_waitcnt lgkmcnt(6)
	v_mfma_f32_16x16x32_bf16 v[40:43], v[158:161], v[166:169], v[40:43]
	s_waitcnt lgkmcnt(5)
	s_mov_b32 m0, s62
	v_mfma_f32_16x16x32_bf16 v[44:47], v[162:165], v[166:169], v[44:47]
	global_load_lds_dwordx4 v146, s[64:65]
	s_waitcnt lgkmcnt(4)
	v_mfma_f32_16x16x32_bf16 v[56:59], v[158:161], v[178:181], v[56:59]
	v_mfma_f32_16x16x32_bf16 v[60:63], v[162:165], v[178:181], v[60:63]
	s_waitcnt lgkmcnt(3)
	v_mfma_f32_16x16x32_bf16 v[72:75], v[158:161], v[222:225], v[72:75]
	v_mfma_f32_16x16x32_bf16 v[76:79], v[162:165], v[222:225], v[76:79]
	s_waitcnt lgkmcnt(2)
	s_mov_b32 m0, s63
	v_mfma_f32_16x16x32_bf16 v[48:51], v[214:217], v[166:169], v[48:51]
	global_load_lds_dwordx4 v146, s[68:69]
	s_waitcnt lgkmcnt(1)
	v_mfma_f32_16x16x32_bf16 v[174:177], v[218:221], v[166:169], v[174:177]
	ds_read_b128 v[166:169], v6 offset:9216
	v_mfma_f32_16x16x32_bf16 v[64:67], v[214:217], v[178:181], v[64:67]
	v_mfma_f32_16x16x32_bf16 v[170:173], v[218:221], v[178:181], v[170:173]
	ds_read_b128 v[178:181], v6 offset:11264
	v_mfma_f32_16x16x32_bf16 v[80:83], v[214:217], v[222:225], v[80:83]
	v_mfma_f32_16x16x32_bf16 v[32:35], v[218:221], v[222:225], v[32:35]
	ds_read_b128 v[222:225], v6 offset:13312
	s_waitcnt lgkmcnt(3)
	v_mfma_f32_16x16x32_bf16 v[88:91], v[158:161], v[226:229], v[88:91]
	v_mfma_f32_16x16x32_bf16 v[92:95], v[162:165], v[226:229], v[92:95]
	v_mfma_f32_16x16x32_bf16 v[96:99], v[214:217], v[226:229], v[96:99]
	v_mfma_f32_16x16x32_bf16 v[36:39], v[218:221], v[226:229], v[36:39]
	ds_read_b128 v[226:229], v6 offset:15360
	s_waitcnt lgkmcnt(3)
	v_mfma_f32_16x16x32_bf16 v[104:107], v[158:161], v[166:169], v[104:107]
	v_mfma_f32_16x16x32_bf16 v[108:111], v[162:165], v[166:169], v[108:111]
	v_mfma_f32_16x16x32_bf16 v[112:115], v[214:217], v[166:169], v[112:115]
	v_mfma_f32_16x16x32_bf16 v[52:55], v[218:221], v[166:169], v[52:55]
	s_waitcnt lgkmcnt(2)
	v_mfma_f32_16x16x32_bf16 v[116:119], v[158:161], v[178:181], v[116:119]
	v_mfma_f32_16x16x32_bf16 v[120:123], v[162:165], v[178:181], v[120:123]
	v_mfma_f32_16x16x32_bf16 v[124:127], v[214:217], v[178:181], v[124:127]
	v_mfma_f32_16x16x32_bf16 v[68:71], v[218:221], v[178:181], v[68:71]
	s_waitcnt lgkmcnt(1)
	v_mfma_f32_16x16x32_bf16 v[128:131], v[158:161], v[222:225], v[128:131]
	v_mfma_f32_16x16x32_bf16 v[132:135], v[162:165], v[222:225], v[132:135]
	v_mfma_f32_16x16x32_bf16 v[136:139], v[214:217], v[222:225], v[136:139]
	v_mfma_f32_16x16x32_bf16 v[84:87], v[218:221], v[222:225], v[84:87]
	s_waitcnt lgkmcnt(0)
	v_mfma_f32_16x16x32_bf16 v[100:103], v[158:161], v[226:229], v[100:103]
	v_mfma_f32_16x16x32_bf16 v[140:143], v[162:165], v[226:229], v[140:143]
	v_mfma_f32_16x16x32_bf16 v[150:153], v[214:217], v[226:229], v[150:153]
	v_mfma_f32_16x16x32_bf16 v[154:157], v[218:221], v[226:229], v[154:157]
	s_add_u32 s64, s0, 0x1000
	s_addc_u32 s65, s1, 0
	s_add_u32 s68, s14, 0x1000
	s_waitcnt vmcnt(0)
	s_barrier
	s_addc_u32 s69, s15, 0
	ds_read_b128 v[158:161], v8
	ds_read_b128 v[162:165], v12
	ds_read_b128 v[166:169], v9
	ds_read_b128 v[178:181], v13
	ds_read_b128 v[214:217], v11
	ds_read_b128 v[218:221], v10
	ds_read_b128 v[222:225], v14
	ds_read_b128 v[226:229], v15
	s_waitcnt lgkmcnt(6)
	v_mfma_f32_16x16x32_bf16 v[40:43], v[158:161], v[162:165], v[40:43]
	s_waitcnt lgkmcnt(5)
	v_mfma_f32_16x16x32_bf16 v[44:47], v[166:169], v[162:165], v[44:47]
	s_waitcnt lgkmcnt(4)
	v_mfma_f32_16x16x32_bf16 v[56:59], v[158:161], v[178:181], v[56:59]
	s_mov_b32 m0, s42
	v_mfma_f32_16x16x32_bf16 v[60:63], v[166:169], v[178:181], v[60:63]
	global_load_lds_dwordx4 v0, s[64:65]
	s_waitcnt lgkmcnt(3)
	v_mfma_f32_16x16x32_bf16 v[48:51], v[214:217], v[162:165], v[48:51]
	v_mfma_f32_16x16x32_bf16 v[64:67], v[214:217], v[178:181], v[64:67]
	s_waitcnt lgkmcnt(2)
	v_mfma_f32_16x16x32_bf16 v[174:177], v[218:221], v[162:165], v[174:177]
	ds_read_b128 v[162:165], v16
	v_mfma_f32_16x16x32_bf16 v[170:173], v[218:221], v[178:181], v[170:173]
	ds_read_b128 v[178:181], v17
	s_waitcnt lgkmcnt(3)
	s_mov_b32 m0, s43
	v_mfma_f32_16x16x32_bf16 v[72:75], v[158:161], v[222:225], v[72:75]
	global_load_lds_dwordx4 v0, s[68:69]
	v_mfma_f32_16x16x32_bf16 v[76:79], v[166:169], v[222:225], v[76:79]
	v_mfma_f32_16x16x32_bf16 v[80:83], v[214:217], v[222:225], v[80:83]
	v_mfma_f32_16x16x32_bf16 v[32:35], v[218:221], v[222:225], v[32:35]
	ds_read_b128 v[222:225], v18
	s_waitcnt lgkmcnt(3)
	v_mfma_f32_16x16x32_bf16 v[88:91], v[158:161], v[226:229], v[88:91]
	s_mov_b32 m0, s44
	v_mfma_f32_16x16x32_bf16 v[92:95], v[166:169], v[226:229], v[92:95]
	global_load_lds_dwordx4 v2, s[64:65]
	v_mfma_f32_16x16x32_bf16 v[96:99], v[214:217], v[226:229], v[96:99]
	v_mfma_f32_16x16x32_bf16 v[36:39], v[218:221], v[226:229], v[36:39]
	ds_read_b128 v[226:229], v19
	s_waitcnt lgkmcnt(3)
	v_mfma_f32_16x16x32_bf16 v[104:107], v[158:161], v[162:165], v[104:107]
	s_waitcnt lgkmcnt(2)
	v_mfma_f32_16x16x32_bf16 v[116:119], v[158:161], v[178:181], v[116:119]
	s_waitcnt lgkmcnt(1)
	s_mov_b32 m0, s45
	v_mfma_f32_16x16x32_bf16 v[128:131], v[158:161], v[222:225], v[128:131]
	global_load_lds_dwordx4 v2, s[68:69]
	s_waitcnt lgkmcnt(0)
	v_mfma_f32_16x16x32_bf16 v[100:103], v[158:161], v[226:229], v[100:103]
	ds_read_b128 v[158:161], v20
	v_mfma_f32_16x16x32_bf16 v[108:111], v[166:169], v[162:165], v[108:111]
	v_mfma_f32_16x16x32_bf16 v[120:123], v[166:169], v[178:181], v[120:123]
	v_mfma_f32_16x16x32_bf16 v[132:135], v[166:169], v[222:225], v[132:135]
	s_mov_b32 m0, s46
	v_mfma_f32_16x16x32_bf16 v[140:143], v[166:169], v[226:229], v[140:143]
	global_load_lds_dwordx4 v4, s[64:65]
	ds_read_b128 v[166:169], v24
	v_mfma_f32_16x16x32_bf16 v[112:115], v[214:217], v[162:165], v[112:115]
	v_mfma_f32_16x16x32_bf16 v[52:55], v[218:221], v[162:165], v[52:55]
	ds_read_b128 v[162:165], v21
	v_mfma_f32_16x16x32_bf16 v[124:127], v[214:217], v[178:181], v[124:127]
	v_mfma_f32_16x16x32_bf16 v[68:71], v[218:221], v[178:181], v[68:71]
	ds_read_b128 v[178:181], v25
	s_mov_b32 m0, s47
	v_mfma_f32_16x16x32_bf16 v[136:139], v[214:217], v[222:225], v[136:139]
	global_load_lds_dwordx4 v4, s[68:69]
	v_mfma_f32_16x16x32_bf16 v[84:87], v[218:221], v[222:225], v[84:87]
	ds_read_b128 v[222:225], v26
	v_mfma_f32_16x16x32_bf16 v[150:153], v[214:217], v[226:229], v[150:153]
	ds_read_b128 v[214:217], v23
	v_mfma_f32_16x16x32_bf16 v[154:157], v[218:221], v[226:229], v[154:157]
	ds_read_b128 v[218:221], v22
	ds_read_b128 v[226:229], v27
	s_waitcnt lgkmcnt(6)
	v_mfma_f32_16x16x32_bf16 v[40:43], v[158:161], v[166:169], v[40:43]
	s_waitcnt lgkmcnt(5)
	s_mov_b32 m0, s49
	v_mfma_f32_16x16x32_bf16 v[44:47], v[162:165], v[166:169], v[44:47]
	global_load_lds_dwordx4 v146, s[64:65]
	s_waitcnt lgkmcnt(4)
	v_mfma_f32_16x16x32_bf16 v[56:59], v[158:161], v[178:181], v[56:59]
	v_mfma_f32_16x16x32_bf16 v[60:63], v[162:165], v[178:181], v[60:63]
	s_waitcnt lgkmcnt(3)
	v_mfma_f32_16x16x32_bf16 v[72:75], v[158:161], v[222:225], v[72:75]
	v_mfma_f32_16x16x32_bf16 v[76:79], v[162:165], v[222:225], v[76:79]
	s_waitcnt lgkmcnt(2)
	s_mov_b32 m0, s50
	v_mfma_f32_16x16x32_bf16 v[48:51], v[214:217], v[166:169], v[48:51]
	global_load_lds_dwordx4 v146, s[68:69]
	s_waitcnt lgkmcnt(1)
	v_mfma_f32_16x16x32_bf16 v[174:177], v[218:221], v[166:169], v[174:177]
	ds_read_b128 v[166:169], v28
	v_mfma_f32_16x16x32_bf16 v[64:67], v[214:217], v[178:181], v[64:67]
	v_mfma_f32_16x16x32_bf16 v[170:173], v[218:221], v[178:181], v[170:173]
	ds_read_b128 v[178:181], v29
	v_mfma_f32_16x16x32_bf16 v[80:83], v[214:217], v[222:225], v[80:83]
	v_mfma_f32_16x16x32_bf16 v[32:35], v[218:221], v[222:225], v[32:35]
	ds_read_b128 v[222:225], v30
	s_waitcnt lgkmcnt(3)
	v_mfma_f32_16x16x32_bf16 v[88:91], v[158:161], v[226:229], v[88:91]
	v_mfma_f32_16x16x32_bf16 v[92:95], v[162:165], v[226:229], v[92:95]
	v_mfma_f32_16x16x32_bf16 v[96:99], v[214:217], v[226:229], v[96:99]
	v_mfma_f32_16x16x32_bf16 v[36:39], v[218:221], v[226:229], v[36:39]
	ds_read_b128 v[226:229], v31
	s_waitcnt lgkmcnt(3)
	v_mfma_f32_16x16x32_bf16 v[104:107], v[158:161], v[166:169], v[104:107]
	v_mfma_f32_16x16x32_bf16 v[108:111], v[162:165], v[166:169], v[108:111]
	v_mfma_f32_16x16x32_bf16 v[112:115], v[214:217], v[166:169], v[112:115]
	v_mfma_f32_16x16x32_bf16 v[52:55], v[218:221], v[166:169], v[52:55]
	s_waitcnt lgkmcnt(2)
	v_mfma_f32_16x16x32_bf16 v[116:119], v[158:161], v[178:181], v[116:119]
	v_mfma_f32_16x16x32_bf16 v[120:123], v[162:165], v[178:181], v[120:123]
	v_mfma_f32_16x16x32_bf16 v[124:127], v[214:217], v[178:181], v[124:127]
	v_mfma_f32_16x16x32_bf16 v[68:71], v[218:221], v[178:181], v[68:71]
	s_waitcnt lgkmcnt(1)
	v_mfma_f32_16x16x32_bf16 v[128:131], v[158:161], v[222:225], v[128:131]
	v_mfma_f32_16x16x32_bf16 v[132:135], v[162:165], v[222:225], v[132:135]
	v_mfma_f32_16x16x32_bf16 v[136:139], v[214:217], v[222:225], v[136:139]
	v_mfma_f32_16x16x32_bf16 v[84:87], v[218:221], v[222:225], v[84:87]
	s_waitcnt lgkmcnt(0)
	v_mfma_f32_16x16x32_bf16 v[100:103], v[158:161], v[226:229], v[100:103]
	v_mfma_f32_16x16x32_bf16 v[140:143], v[162:165], v[226:229], v[140:143]
	v_mfma_f32_16x16x32_bf16 v[150:153], v[214:217], v[226:229], v[150:153]
	v_mfma_f32_16x16x32_bf16 v[154:157], v[218:221], v[226:229], v[154:157]
	s_add_u32 s64, s0, 0x1080
	s_addc_u32 s65, s1, 0
	s_add_u32 s68, s14, 0x1080
	s_waitcnt vmcnt(0)
	s_barrier
	s_addc_u32 s69, s15, 0
	ds_read_b128 v[158:161], v7 offset:32768
	ds_read_b128 v[162:165], v6
	ds_read_b128 v[166:169], v7 offset:34816
	ds_read_b128 v[178:181], v6 offset:2048
	ds_read_b128 v[214:217], v7 offset:36864
	ds_read_b128 v[218:221], v7 offset:38912
	ds_read_b128 v[222:225], v6 offset:4096
	ds_read_b128 v[226:229], v6 offset:6144
	s_waitcnt lgkmcnt(6)
	v_mfma_f32_16x16x32_bf16 v[40:43], v[158:161], v[162:165], v[40:43]
	s_waitcnt lgkmcnt(5)
	v_mfma_f32_16x16x32_bf16 v[44:47], v[166:169], v[162:165], v[44:47]
	s_waitcnt lgkmcnt(4)
	v_mfma_f32_16x16x32_bf16 v[56:59], v[158:161], v[178:181], v[56:59]
	s_mov_b32 m0, s52
	v_mfma_f32_16x16x32_bf16 v[60:63], v[166:169], v[178:181], v[60:63]
	global_load_lds_dwordx4 v0, s[64:65]
	s_waitcnt lgkmcnt(3)
	v_mfma_f32_16x16x32_bf16 v[48:51], v[214:217], v[162:165], v[48:51]
	v_mfma_f32_16x16x32_bf16 v[64:67], v[214:217], v[178:181], v[64:67]
	s_waitcnt lgkmcnt(2)
	v_mfma_f32_16x16x32_bf16 v[174:177], v[218:221], v[162:165], v[174:177]
	ds_read_b128 v[162:165], v6 offset:8192
	v_mfma_f32_16x16x32_bf16 v[170:173], v[218:221], v[178:181], v[170:173]
	ds_read_b128 v[178:181], v6 offset:10240
	s_waitcnt lgkmcnt(3)
	s_mov_b32 m0, s51
	v_mfma_f32_16x16x32_bf16 v[72:75], v[158:161], v[222:225], v[72:75]
	global_load_lds_dwordx4 v0, s[68:69]
	v_mfma_f32_16x16x32_bf16 v[76:79], v[166:169], v[222:225], v[76:79]
	v_mfma_f32_16x16x32_bf16 v[80:83], v[214:217], v[222:225], v[80:83]
	v_mfma_f32_16x16x32_bf16 v[32:35], v[218:221], v[222:225], v[32:35]
	ds_read_b128 v[222:225], v6 offset:12288
	s_waitcnt lgkmcnt(3)
	v_mfma_f32_16x16x32_bf16 v[88:91], v[158:161], v[226:229], v[88:91]
	s_mov_b32 m0, s53
	v_mfma_f32_16x16x32_bf16 v[92:95], v[166:169], v[226:229], v[92:95]
	global_load_lds_dwordx4 v2, s[64:65]
	v_mfma_f32_16x16x32_bf16 v[96:99], v[214:217], v[226:229], v[96:99]
	v_mfma_f32_16x16x32_bf16 v[36:39], v[218:221], v[226:229], v[36:39]
	ds_read_b128 v[226:229], v6 offset:14336
	s_waitcnt lgkmcnt(3)
	v_mfma_f32_16x16x32_bf16 v[104:107], v[158:161], v[162:165], v[104:107]
	s_waitcnt lgkmcnt(2)
	v_mfma_f32_16x16x32_bf16 v[116:119], v[158:161], v[178:181], v[116:119]
	s_waitcnt lgkmcnt(1)
	s_mov_b32 m0, s54
	v_mfma_f32_16x16x32_bf16 v[128:131], v[158:161], v[222:225], v[128:131]
	global_load_lds_dwordx4 v2, s[68:69]
	s_waitcnt lgkmcnt(0)
	v_mfma_f32_16x16x32_bf16 v[100:103], v[158:161], v[226:229], v[100:103]
	ds_read_b128 v[158:161], v7 offset:33792
	v_mfma_f32_16x16x32_bf16 v[108:111], v[166:169], v[162:165], v[108:111]
	v_mfma_f32_16x16x32_bf16 v[120:123], v[166:169], v[178:181], v[120:123]
	v_mfma_f32_16x16x32_bf16 v[132:135], v[166:169], v[222:225], v[132:135]
	s_mov_b32 m0, s55
	v_mfma_f32_16x16x32_bf16 v[140:143], v[166:169], v[226:229], v[140:143]
	global_load_lds_dwordx4 v4, s[64:65]
	ds_read_b128 v[166:169], v6 offset:1024
	v_mfma_f32_16x16x32_bf16 v[112:115], v[214:217], v[162:165], v[112:115]
	v_mfma_f32_16x16x32_bf16 v[52:55], v[218:221], v[162:165], v[52:55]
	ds_read_b128 v[162:165], v7 offset:35840
	v_mfma_f32_16x16x32_bf16 v[124:127], v[214:217], v[178:181], v[124:127]
	v_mfma_f32_16x16x32_bf16 v[68:71], v[218:221], v[178:181], v[68:71]
	ds_read_b128 v[178:181], v6 offset:3072
	s_mov_b32 m0, s58
	v_mfma_f32_16x16x32_bf16 v[136:139], v[214:217], v[222:225], v[136:139]
	global_load_lds_dwordx4 v4, s[68:69]
	v_mfma_f32_16x16x32_bf16 v[84:87], v[218:221], v[222:225], v[84:87]
	ds_read_b128 v[222:225], v6 offset:5120
	v_mfma_f32_16x16x32_bf16 v[150:153], v[214:217], v[226:229], v[150:153]
	ds_read_b128 v[214:217], v7 offset:37888
	v_mfma_f32_16x16x32_bf16 v[154:157], v[218:221], v[226:229], v[154:157]
	ds_read_b128 v[218:221], v7 offset:39936
	ds_read_b128 v[226:229], v6 offset:7168
	s_waitcnt lgkmcnt(6)
	v_mfma_f32_16x16x32_bf16 v[40:43], v[158:161], v[166:169], v[40:43]
	s_waitcnt lgkmcnt(5)
	s_mov_b32 m0, s62
	v_mfma_f32_16x16x32_bf16 v[44:47], v[162:165], v[166:169], v[44:47]
	global_load_lds_dwordx4 v146, s[64:65]
	s_waitcnt lgkmcnt(4)
	v_mfma_f32_16x16x32_bf16 v[56:59], v[158:161], v[178:181], v[56:59]
	v_mfma_f32_16x16x32_bf16 v[60:63], v[162:165], v[178:181], v[60:63]
	s_waitcnt lgkmcnt(3)
	v_mfma_f32_16x16x32_bf16 v[72:75], v[158:161], v[222:225], v[72:75]
	v_mfma_f32_16x16x32_bf16 v[76:79], v[162:165], v[222:225], v[76:79]
	s_waitcnt lgkmcnt(2)
	s_mov_b32 m0, s63
	v_mfma_f32_16x16x32_bf16 v[48:51], v[214:217], v[166:169], v[48:51]
	global_load_lds_dwordx4 v146, s[68:69]
	s_waitcnt lgkmcnt(1)
	v_mfma_f32_16x16x32_bf16 v[174:177], v[218:221], v[166:169], v[174:177]
	ds_read_b128 v[166:169], v6 offset:9216
	v_mfma_f32_16x16x32_bf16 v[64:67], v[214:217], v[178:181], v[64:67]
	v_mfma_f32_16x16x32_bf16 v[170:173], v[218:221], v[178:181], v[170:173]
	ds_read_b128 v[178:181], v6 offset:11264
	v_mfma_f32_16x16x32_bf16 v[80:83], v[214:217], v[222:225], v[80:83]
	v_mfma_f32_16x16x32_bf16 v[32:35], v[218:221], v[222:225], v[32:35]
	ds_read_b128 v[222:225], v6 offset:13312
	s_waitcnt lgkmcnt(3)
	v_mfma_f32_16x16x32_bf16 v[88:91], v[158:161], v[226:229], v[88:91]
	v_mfma_f32_16x16x32_bf16 v[92:95], v[162:165], v[226:229], v[92:95]
	v_mfma_f32_16x16x32_bf16 v[96:99], v[214:217], v[226:229], v[96:99]
	v_mfma_f32_16x16x32_bf16 v[36:39], v[218:221], v[226:229], v[36:39]
	ds_read_b128 v[226:229], v6 offset:15360
	s_waitcnt lgkmcnt(3)
	v_mfma_f32_16x16x32_bf16 v[104:107], v[158:161], v[166:169], v[104:107]
	v_mfma_f32_16x16x32_bf16 v[108:111], v[162:165], v[166:169], v[108:111]
	v_mfma_f32_16x16x32_bf16 v[112:115], v[214:217], v[166:169], v[112:115]
	v_mfma_f32_16x16x32_bf16 v[52:55], v[218:221], v[166:169], v[52:55]
	s_waitcnt lgkmcnt(2)
	v_mfma_f32_16x16x32_bf16 v[116:119], v[158:161], v[178:181], v[116:119]
	v_mfma_f32_16x16x32_bf16 v[120:123], v[162:165], v[178:181], v[120:123]
	v_mfma_f32_16x16x32_bf16 v[124:127], v[214:217], v[178:181], v[124:127]
	v_mfma_f32_16x16x32_bf16 v[68:71], v[218:221], v[178:181], v[68:71]
	s_waitcnt lgkmcnt(1)
	v_mfma_f32_16x16x32_bf16 v[128:131], v[158:161], v[222:225], v[128:131]
	v_mfma_f32_16x16x32_bf16 v[132:135], v[162:165], v[222:225], v[132:135]
	v_mfma_f32_16x16x32_bf16 v[136:139], v[214:217], v[222:225], v[136:139]
	v_mfma_f32_16x16x32_bf16 v[84:87], v[218:221], v[222:225], v[84:87]
	s_waitcnt lgkmcnt(0)
	v_mfma_f32_16x16x32_bf16 v[100:103], v[158:161], v[226:229], v[100:103]
	v_mfma_f32_16x16x32_bf16 v[140:143], v[162:165], v[226:229], v[140:143]
	v_mfma_f32_16x16x32_bf16 v[150:153], v[214:217], v[226:229], v[150:153]
	v_mfma_f32_16x16x32_bf16 v[154:157], v[218:221], v[226:229], v[154:157]
	s_add_u32 s64, s0, 0x1100
	s_addc_u32 s65, s1, 0
	s_add_u32 s68, s14, 0x1100
	s_waitcnt vmcnt(0)
	s_barrier
	s_addc_u32 s69, s15, 0
	ds_read_b128 v[158:161], v8
	ds_read_b128 v[162:165], v12
	ds_read_b128 v[166:169], v9
	ds_read_b128 v[178:181], v13
	ds_read_b128 v[214:217], v11
	ds_read_b128 v[218:221], v10
	ds_read_b128 v[222:225], v14
	ds_read_b128 v[226:229], v15
	s_waitcnt lgkmcnt(6)
	v_mfma_f32_16x16x32_bf16 v[40:43], v[158:161], v[162:165], v[40:43]
	s_waitcnt lgkmcnt(5)
	v_mfma_f32_16x16x32_bf16 v[44:47], v[166:169], v[162:165], v[44:47]
	s_waitcnt lgkmcnt(4)
	v_mfma_f32_16x16x32_bf16 v[56:59], v[158:161], v[178:181], v[56:59]
	s_mov_b32 m0, s42
	v_mfma_f32_16x16x32_bf16 v[60:63], v[166:169], v[178:181], v[60:63]
	global_load_lds_dwordx4 v0, s[64:65]
	s_waitcnt lgkmcnt(3)
	v_mfma_f32_16x16x32_bf16 v[48:51], v[214:217], v[162:165], v[48:51]
	v_mfma_f32_16x16x32_bf16 v[64:67], v[214:217], v[178:181], v[64:67]
	s_waitcnt lgkmcnt(2)
	v_mfma_f32_16x16x32_bf16 v[174:177], v[218:221], v[162:165], v[174:177]
	ds_read_b128 v[162:165], v16
	v_mfma_f32_16x16x32_bf16 v[170:173], v[218:221], v[178:181], v[170:173]
	ds_read_b128 v[178:181], v17
	s_waitcnt lgkmcnt(3)
	s_mov_b32 m0, s43
	v_mfma_f32_16x16x32_bf16 v[72:75], v[158:161], v[222:225], v[72:75]
	global_load_lds_dwordx4 v0, s[68:69]
	v_mfma_f32_16x16x32_bf16 v[76:79], v[166:169], v[222:225], v[76:79]
	v_mfma_f32_16x16x32_bf16 v[80:83], v[214:217], v[222:225], v[80:83]
	v_mfma_f32_16x16x32_bf16 v[32:35], v[218:221], v[222:225], v[32:35]
	ds_read_b128 v[222:225], v18
	s_waitcnt lgkmcnt(3)
	v_mfma_f32_16x16x32_bf16 v[88:91], v[158:161], v[226:229], v[88:91]
	s_mov_b32 m0, s44
	v_mfma_f32_16x16x32_bf16 v[92:95], v[166:169], v[226:229], v[92:95]
	global_load_lds_dwordx4 v2, s[64:65]
	v_mfma_f32_16x16x32_bf16 v[96:99], v[214:217], v[226:229], v[96:99]
	v_mfma_f32_16x16x32_bf16 v[36:39], v[218:221], v[226:229], v[36:39]
	ds_read_b128 v[226:229], v19
	s_waitcnt lgkmcnt(3)
	v_mfma_f32_16x16x32_bf16 v[104:107], v[158:161], v[162:165], v[104:107]
	s_waitcnt lgkmcnt(2)
	v_mfma_f32_16x16x32_bf16 v[116:119], v[158:161], v[178:181], v[116:119]
	s_waitcnt lgkmcnt(1)
	s_mov_b32 m0, s45
	v_mfma_f32_16x16x32_bf16 v[128:131], v[158:161], v[222:225], v[128:131]
	global_load_lds_dwordx4 v2, s[68:69]
	s_waitcnt lgkmcnt(0)
	v_mfma_f32_16x16x32_bf16 v[100:103], v[158:161], v[226:229], v[100:103]
	ds_read_b128 v[158:161], v20
	v_mfma_f32_16x16x32_bf16 v[108:111], v[166:169], v[162:165], v[108:111]
	v_mfma_f32_16x16x32_bf16 v[120:123], v[166:169], v[178:181], v[120:123]
	v_mfma_f32_16x16x32_bf16 v[132:135], v[166:169], v[222:225], v[132:135]
	s_mov_b32 m0, s46
	v_mfma_f32_16x16x32_bf16 v[140:143], v[166:169], v[226:229], v[140:143]
	global_load_lds_dwordx4 v4, s[64:65]
	ds_read_b128 v[166:169], v24
	v_mfma_f32_16x16x32_bf16 v[112:115], v[214:217], v[162:165], v[112:115]
	v_mfma_f32_16x16x32_bf16 v[52:55], v[218:221], v[162:165], v[52:55]
	ds_read_b128 v[162:165], v21
	v_mfma_f32_16x16x32_bf16 v[124:127], v[214:217], v[178:181], v[124:127]
	v_mfma_f32_16x16x32_bf16 v[68:71], v[218:221], v[178:181], v[68:71]
	ds_read_b128 v[178:181], v25
	s_mov_b32 m0, s47
	v_mfma_f32_16x16x32_bf16 v[136:139], v[214:217], v[222:225], v[136:139]
	global_load_lds_dwordx4 v4, s[68:69]
	v_mfma_f32_16x16x32_bf16 v[84:87], v[218:221], v[222:225], v[84:87]
	ds_read_b128 v[222:225], v26
	v_mfma_f32_16x16x32_bf16 v[150:153], v[214:217], v[226:229], v[150:153]
	ds_read_b128 v[214:217], v23
	v_mfma_f32_16x16x32_bf16 v[154:157], v[218:221], v[226:229], v[154:157]
	ds_read_b128 v[218:221], v22
	ds_read_b128 v[226:229], v27
	s_waitcnt lgkmcnt(6)
	v_mfma_f32_16x16x32_bf16 v[40:43], v[158:161], v[166:169], v[40:43]
	s_waitcnt lgkmcnt(5)
	s_mov_b32 m0, s49
	v_mfma_f32_16x16x32_bf16 v[44:47], v[162:165], v[166:169], v[44:47]
	global_load_lds_dwordx4 v146, s[64:65]
	s_waitcnt lgkmcnt(4)
	v_mfma_f32_16x16x32_bf16 v[56:59], v[158:161], v[178:181], v[56:59]
	v_mfma_f32_16x16x32_bf16 v[60:63], v[162:165], v[178:181], v[60:63]
	s_waitcnt lgkmcnt(3)
	v_mfma_f32_16x16x32_bf16 v[72:75], v[158:161], v[222:225], v[72:75]
	v_mfma_f32_16x16x32_bf16 v[76:79], v[162:165], v[222:225], v[76:79]
	s_waitcnt lgkmcnt(2)
	s_mov_b32 m0, s50
	v_mfma_f32_16x16x32_bf16 v[48:51], v[214:217], v[166:169], v[48:51]
	global_load_lds_dwordx4 v146, s[68:69]
	s_waitcnt lgkmcnt(1)
	v_mfma_f32_16x16x32_bf16 v[174:177], v[218:221], v[166:169], v[174:177]
	ds_read_b128 v[166:169], v28
	v_mfma_f32_16x16x32_bf16 v[64:67], v[214:217], v[178:181], v[64:67]
	v_mfma_f32_16x16x32_bf16 v[170:173], v[218:221], v[178:181], v[170:173]
	ds_read_b128 v[178:181], v29
	v_mfma_f32_16x16x32_bf16 v[80:83], v[214:217], v[222:225], v[80:83]
	v_mfma_f32_16x16x32_bf16 v[32:35], v[218:221], v[222:225], v[32:35]
	ds_read_b128 v[222:225], v30
	s_waitcnt lgkmcnt(3)
	v_mfma_f32_16x16x32_bf16 v[88:91], v[158:161], v[226:229], v[88:91]
	v_mfma_f32_16x16x32_bf16 v[92:95], v[162:165], v[226:229], v[92:95]
	v_mfma_f32_16x16x32_bf16 v[96:99], v[214:217], v[226:229], v[96:99]
	v_mfma_f32_16x16x32_bf16 v[36:39], v[218:221], v[226:229], v[36:39]
	ds_read_b128 v[226:229], v31
	s_waitcnt lgkmcnt(3)
	v_mfma_f32_16x16x32_bf16 v[104:107], v[158:161], v[166:169], v[104:107]
	v_mfma_f32_16x16x32_bf16 v[108:111], v[162:165], v[166:169], v[108:111]
	v_mfma_f32_16x16x32_bf16 v[112:115], v[214:217], v[166:169], v[112:115]
	v_mfma_f32_16x16x32_bf16 v[52:55], v[218:221], v[166:169], v[52:55]
	s_waitcnt lgkmcnt(2)
	v_mfma_f32_16x16x32_bf16 v[116:119], v[158:161], v[178:181], v[116:119]
	v_mfma_f32_16x16x32_bf16 v[120:123], v[162:165], v[178:181], v[120:123]
	v_mfma_f32_16x16x32_bf16 v[124:127], v[214:217], v[178:181], v[124:127]
	v_mfma_f32_16x16x32_bf16 v[68:71], v[218:221], v[178:181], v[68:71]
	s_waitcnt lgkmcnt(1)
	v_mfma_f32_16x16x32_bf16 v[128:131], v[158:161], v[222:225], v[128:131]
	v_mfma_f32_16x16x32_bf16 v[132:135], v[162:165], v[222:225], v[132:135]
	v_mfma_f32_16x16x32_bf16 v[136:139], v[214:217], v[222:225], v[136:139]
	v_mfma_f32_16x16x32_bf16 v[84:87], v[218:221], v[222:225], v[84:87]
	s_waitcnt lgkmcnt(0)
	v_mfma_f32_16x16x32_bf16 v[100:103], v[158:161], v[226:229], v[100:103]
	v_mfma_f32_16x16x32_bf16 v[140:143], v[162:165], v[226:229], v[140:143]
	v_mfma_f32_16x16x32_bf16 v[150:153], v[214:217], v[226:229], v[150:153]
	v_mfma_f32_16x16x32_bf16 v[154:157], v[218:221], v[226:229], v[154:157]
	s_add_u32 s64, s0, 0x1180
	s_addc_u32 s65, s1, 0
	s_add_u32 s68, s14, 0x1180
	s_waitcnt vmcnt(0)
	s_barrier
	s_addc_u32 s69, s15, 0
	ds_read_b128 v[158:161], v7 offset:32768
	ds_read_b128 v[162:165], v6
	ds_read_b128 v[166:169], v7 offset:34816
	ds_read_b128 v[178:181], v6 offset:2048
	ds_read_b128 v[214:217], v7 offset:36864
	ds_read_b128 v[218:221], v7 offset:38912
	ds_read_b128 v[222:225], v6 offset:4096
	ds_read_b128 v[226:229], v6 offset:6144
	s_waitcnt lgkmcnt(6)
	v_mfma_f32_16x16x32_bf16 v[40:43], v[158:161], v[162:165], v[40:43]
	s_waitcnt lgkmcnt(5)
	v_mfma_f32_16x16x32_bf16 v[44:47], v[166:169], v[162:165], v[44:47]
	s_waitcnt lgkmcnt(4)
	v_mfma_f32_16x16x32_bf16 v[56:59], v[158:161], v[178:181], v[56:59]
	s_mov_b32 m0, s52
	v_mfma_f32_16x16x32_bf16 v[60:63], v[166:169], v[178:181], v[60:63]
	global_load_lds_dwordx4 v0, s[64:65]
	s_waitcnt lgkmcnt(3)
	v_mfma_f32_16x16x32_bf16 v[48:51], v[214:217], v[162:165], v[48:51]
	v_mfma_f32_16x16x32_bf16 v[64:67], v[214:217], v[178:181], v[64:67]
	s_waitcnt lgkmcnt(2)
	v_mfma_f32_16x16x32_bf16 v[174:177], v[218:221], v[162:165], v[174:177]
	ds_read_b128 v[162:165], v6 offset:8192
	v_mfma_f32_16x16x32_bf16 v[170:173], v[218:221], v[178:181], v[170:173]
	ds_read_b128 v[178:181], v6 offset:10240
	s_waitcnt lgkmcnt(3)
	s_mov_b32 m0, s51
	v_mfma_f32_16x16x32_bf16 v[72:75], v[158:161], v[222:225], v[72:75]
	global_load_lds_dwordx4 v0, s[68:69]
	v_mfma_f32_16x16x32_bf16 v[76:79], v[166:169], v[222:225], v[76:79]
	v_mfma_f32_16x16x32_bf16 v[80:83], v[214:217], v[222:225], v[80:83]
	v_mfma_f32_16x16x32_bf16 v[32:35], v[218:221], v[222:225], v[32:35]
	ds_read_b128 v[222:225], v6 offset:12288
	s_waitcnt lgkmcnt(3)
	v_mfma_f32_16x16x32_bf16 v[88:91], v[158:161], v[226:229], v[88:91]
	s_mov_b32 m0, s53
	v_mfma_f32_16x16x32_bf16 v[92:95], v[166:169], v[226:229], v[92:95]
	global_load_lds_dwordx4 v2, s[64:65]
	v_mfma_f32_16x16x32_bf16 v[96:99], v[214:217], v[226:229], v[96:99]
	v_mfma_f32_16x16x32_bf16 v[36:39], v[218:221], v[226:229], v[36:39]
	ds_read_b128 v[226:229], v6 offset:14336
	s_waitcnt lgkmcnt(3)
	v_mfma_f32_16x16x32_bf16 v[104:107], v[158:161], v[162:165], v[104:107]
	s_waitcnt lgkmcnt(2)
	v_mfma_f32_16x16x32_bf16 v[116:119], v[158:161], v[178:181], v[116:119]
	s_waitcnt lgkmcnt(1)
	s_mov_b32 m0, s54
	v_mfma_f32_16x16x32_bf16 v[128:131], v[158:161], v[222:225], v[128:131]
	global_load_lds_dwordx4 v2, s[68:69]
	s_waitcnt lgkmcnt(0)
	v_mfma_f32_16x16x32_bf16 v[100:103], v[158:161], v[226:229], v[100:103]
	ds_read_b128 v[158:161], v7 offset:33792
	v_mfma_f32_16x16x32_bf16 v[108:111], v[166:169], v[162:165], v[108:111]
	v_mfma_f32_16x16x32_bf16 v[120:123], v[166:169], v[178:181], v[120:123]
	v_mfma_f32_16x16x32_bf16 v[132:135], v[166:169], v[222:225], v[132:135]
	s_mov_b32 m0, s55
	v_mfma_f32_16x16x32_bf16 v[140:143], v[166:169], v[226:229], v[140:143]
	global_load_lds_dwordx4 v4, s[64:65]
	ds_read_b128 v[166:169], v6 offset:1024
	v_mfma_f32_16x16x32_bf16 v[112:115], v[214:217], v[162:165], v[112:115]
	v_mfma_f32_16x16x32_bf16 v[52:55], v[218:221], v[162:165], v[52:55]
	ds_read_b128 v[162:165], v7 offset:35840
	v_mfma_f32_16x16x32_bf16 v[124:127], v[214:217], v[178:181], v[124:127]
	v_mfma_f32_16x16x32_bf16 v[68:71], v[218:221], v[178:181], v[68:71]
	ds_read_b128 v[178:181], v6 offset:3072
	s_mov_b32 m0, s58
	v_mfma_f32_16x16x32_bf16 v[136:139], v[214:217], v[222:225], v[136:139]
	global_load_lds_dwordx4 v4, s[68:69]
	v_mfma_f32_16x16x32_bf16 v[84:87], v[218:221], v[222:225], v[84:87]
	ds_read_b128 v[222:225], v6 offset:5120
	v_mfma_f32_16x16x32_bf16 v[150:153], v[214:217], v[226:229], v[150:153]
	ds_read_b128 v[214:217], v7 offset:37888
	v_mfma_f32_16x16x32_bf16 v[154:157], v[218:221], v[226:229], v[154:157]
	ds_read_b128 v[218:221], v7 offset:39936
	ds_read_b128 v[226:229], v6 offset:7168
	s_waitcnt lgkmcnt(6)
	v_mfma_f32_16x16x32_bf16 v[40:43], v[158:161], v[166:169], v[40:43]
	s_waitcnt lgkmcnt(5)
	s_mov_b32 m0, s62
	v_mfma_f32_16x16x32_bf16 v[44:47], v[162:165], v[166:169], v[44:47]
	global_load_lds_dwordx4 v146, s[64:65]
	s_waitcnt lgkmcnt(4)
	v_mfma_f32_16x16x32_bf16 v[56:59], v[158:161], v[178:181], v[56:59]
	v_mfma_f32_16x16x32_bf16 v[60:63], v[162:165], v[178:181], v[60:63]
	s_waitcnt lgkmcnt(3)
	v_mfma_f32_16x16x32_bf16 v[72:75], v[158:161], v[222:225], v[72:75]
	v_mfma_f32_16x16x32_bf16 v[76:79], v[162:165], v[222:225], v[76:79]
	s_waitcnt lgkmcnt(2)
	s_mov_b32 m0, s63
	v_mfma_f32_16x16x32_bf16 v[48:51], v[214:217], v[166:169], v[48:51]
	global_load_lds_dwordx4 v146, s[68:69]
	s_waitcnt lgkmcnt(1)
	v_mfma_f32_16x16x32_bf16 v[174:177], v[218:221], v[166:169], v[174:177]
	ds_read_b128 v[166:169], v6 offset:9216
	v_mfma_f32_16x16x32_bf16 v[64:67], v[214:217], v[178:181], v[64:67]
	v_mfma_f32_16x16x32_bf16 v[170:173], v[218:221], v[178:181], v[170:173]
	ds_read_b128 v[178:181], v6 offset:11264
	v_mfma_f32_16x16x32_bf16 v[80:83], v[214:217], v[222:225], v[80:83]
	v_mfma_f32_16x16x32_bf16 v[32:35], v[218:221], v[222:225], v[32:35]
	ds_read_b128 v[222:225], v6 offset:13312
	s_waitcnt lgkmcnt(3)
	v_mfma_f32_16x16x32_bf16 v[88:91], v[158:161], v[226:229], v[88:91]
	v_mfma_f32_16x16x32_bf16 v[92:95], v[162:165], v[226:229], v[92:95]
	v_mfma_f32_16x16x32_bf16 v[96:99], v[214:217], v[226:229], v[96:99]
	v_mfma_f32_16x16x32_bf16 v[36:39], v[218:221], v[226:229], v[36:39]
	ds_read_b128 v[226:229], v6 offset:15360
	s_waitcnt lgkmcnt(3)
	v_mfma_f32_16x16x32_bf16 v[104:107], v[158:161], v[166:169], v[104:107]
	v_mfma_f32_16x16x32_bf16 v[108:111], v[162:165], v[166:169], v[108:111]
	v_mfma_f32_16x16x32_bf16 v[112:115], v[214:217], v[166:169], v[112:115]
	v_mfma_f32_16x16x32_bf16 v[52:55], v[218:221], v[166:169], v[52:55]
	s_waitcnt lgkmcnt(2)
	v_mfma_f32_16x16x32_bf16 v[116:119], v[158:161], v[178:181], v[116:119]
	v_mfma_f32_16x16x32_bf16 v[120:123], v[162:165], v[178:181], v[120:123]
	v_mfma_f32_16x16x32_bf16 v[124:127], v[214:217], v[178:181], v[124:127]
	v_mfma_f32_16x16x32_bf16 v[68:71], v[218:221], v[178:181], v[68:71]
	s_waitcnt lgkmcnt(1)
	v_mfma_f32_16x16x32_bf16 v[128:131], v[158:161], v[222:225], v[128:131]
	v_mfma_f32_16x16x32_bf16 v[132:135], v[162:165], v[222:225], v[132:135]
	v_mfma_f32_16x16x32_bf16 v[136:139], v[214:217], v[222:225], v[136:139]
	v_mfma_f32_16x16x32_bf16 v[84:87], v[218:221], v[222:225], v[84:87]
	s_waitcnt lgkmcnt(0)
	v_mfma_f32_16x16x32_bf16 v[100:103], v[158:161], v[226:229], v[100:103]
	v_mfma_f32_16x16x32_bf16 v[140:143], v[162:165], v[226:229], v[140:143]
	v_mfma_f32_16x16x32_bf16 v[150:153], v[214:217], v[226:229], v[150:153]
	v_mfma_f32_16x16x32_bf16 v[154:157], v[218:221], v[226:229], v[154:157]
	s_add_u32 s64, s0, 0x1200
	s_addc_u32 s65, s1, 0
	s_add_u32 s68, s14, 0x1200
	s_waitcnt vmcnt(0)
	s_barrier
	s_addc_u32 s69, s15, 0
	ds_read_b128 v[158:161], v8
	ds_read_b128 v[162:165], v12
	ds_read_b128 v[166:169], v9
	ds_read_b128 v[178:181], v13
	ds_read_b128 v[214:217], v11
	ds_read_b128 v[218:221], v10
	ds_read_b128 v[222:225], v14
	ds_read_b128 v[226:229], v15
	s_waitcnt lgkmcnt(6)
	v_mfma_f32_16x16x32_bf16 v[40:43], v[158:161], v[162:165], v[40:43]
	s_waitcnt lgkmcnt(5)
	v_mfma_f32_16x16x32_bf16 v[44:47], v[166:169], v[162:165], v[44:47]
	s_waitcnt lgkmcnt(4)
	v_mfma_f32_16x16x32_bf16 v[56:59], v[158:161], v[178:181], v[56:59]
	s_mov_b32 m0, s42
	v_mfma_f32_16x16x32_bf16 v[60:63], v[166:169], v[178:181], v[60:63]
	global_load_lds_dwordx4 v0, s[64:65]
	s_waitcnt lgkmcnt(3)
	v_mfma_f32_16x16x32_bf16 v[48:51], v[214:217], v[162:165], v[48:51]
	v_mfma_f32_16x16x32_bf16 v[64:67], v[214:217], v[178:181], v[64:67]
	s_waitcnt lgkmcnt(2)
	v_mfma_f32_16x16x32_bf16 v[174:177], v[218:221], v[162:165], v[174:177]
	ds_read_b128 v[162:165], v16
	v_mfma_f32_16x16x32_bf16 v[170:173], v[218:221], v[178:181], v[170:173]
	ds_read_b128 v[178:181], v17
	s_waitcnt lgkmcnt(3)
	s_mov_b32 m0, s43
	v_mfma_f32_16x16x32_bf16 v[72:75], v[158:161], v[222:225], v[72:75]
	global_load_lds_dwordx4 v0, s[68:69]
	v_mfma_f32_16x16x32_bf16 v[76:79], v[166:169], v[222:225], v[76:79]
	v_mfma_f32_16x16x32_bf16 v[80:83], v[214:217], v[222:225], v[80:83]
	v_mfma_f32_16x16x32_bf16 v[32:35], v[218:221], v[222:225], v[32:35]
	ds_read_b128 v[222:225], v18
	s_waitcnt lgkmcnt(3)
	v_mfma_f32_16x16x32_bf16 v[88:91], v[158:161], v[226:229], v[88:91]
	s_mov_b32 m0, s44
	v_mfma_f32_16x16x32_bf16 v[92:95], v[166:169], v[226:229], v[92:95]
	global_load_lds_dwordx4 v2, s[64:65]
	v_mfma_f32_16x16x32_bf16 v[96:99], v[214:217], v[226:229], v[96:99]
	v_mfma_f32_16x16x32_bf16 v[36:39], v[218:221], v[226:229], v[36:39]
	ds_read_b128 v[226:229], v19
	s_waitcnt lgkmcnt(3)
	v_mfma_f32_16x16x32_bf16 v[104:107], v[158:161], v[162:165], v[104:107]
	s_waitcnt lgkmcnt(2)
	v_mfma_f32_16x16x32_bf16 v[116:119], v[158:161], v[178:181], v[116:119]
	s_waitcnt lgkmcnt(1)
	s_mov_b32 m0, s45
	v_mfma_f32_16x16x32_bf16 v[128:131], v[158:161], v[222:225], v[128:131]
	global_load_lds_dwordx4 v2, s[68:69]
	s_waitcnt lgkmcnt(0)
	v_mfma_f32_16x16x32_bf16 v[100:103], v[158:161], v[226:229], v[100:103]
	ds_read_b128 v[158:161], v20
	v_mfma_f32_16x16x32_bf16 v[108:111], v[166:169], v[162:165], v[108:111]
	v_mfma_f32_16x16x32_bf16 v[120:123], v[166:169], v[178:181], v[120:123]
	v_mfma_f32_16x16x32_bf16 v[132:135], v[166:169], v[222:225], v[132:135]
	s_mov_b32 m0, s46
	v_mfma_f32_16x16x32_bf16 v[140:143], v[166:169], v[226:229], v[140:143]
	global_load_lds_dwordx4 v4, s[64:65]
	ds_read_b128 v[166:169], v24
	v_mfma_f32_16x16x32_bf16 v[112:115], v[214:217], v[162:165], v[112:115]
	v_mfma_f32_16x16x32_bf16 v[52:55], v[218:221], v[162:165], v[52:55]
	ds_read_b128 v[162:165], v21
	v_mfma_f32_16x16x32_bf16 v[124:127], v[214:217], v[178:181], v[124:127]
	v_mfma_f32_16x16x32_bf16 v[68:71], v[218:221], v[178:181], v[68:71]
	ds_read_b128 v[178:181], v25
	s_mov_b32 m0, s47
	v_mfma_f32_16x16x32_bf16 v[136:139], v[214:217], v[222:225], v[136:139]
	global_load_lds_dwordx4 v4, s[68:69]
	v_mfma_f32_16x16x32_bf16 v[84:87], v[218:221], v[222:225], v[84:87]
	ds_read_b128 v[222:225], v26
	v_mfma_f32_16x16x32_bf16 v[150:153], v[214:217], v[226:229], v[150:153]
	ds_read_b128 v[214:217], v23
	v_mfma_f32_16x16x32_bf16 v[154:157], v[218:221], v[226:229], v[154:157]
	ds_read_b128 v[218:221], v22
	ds_read_b128 v[226:229], v27
	s_waitcnt lgkmcnt(6)
	v_mfma_f32_16x16x32_bf16 v[40:43], v[158:161], v[166:169], v[40:43]
	s_waitcnt lgkmcnt(5)
	s_mov_b32 m0, s49
	v_mfma_f32_16x16x32_bf16 v[44:47], v[162:165], v[166:169], v[44:47]
	global_load_lds_dwordx4 v146, s[64:65]
	s_waitcnt lgkmcnt(4)
	v_mfma_f32_16x16x32_bf16 v[56:59], v[158:161], v[178:181], v[56:59]
	v_mfma_f32_16x16x32_bf16 v[60:63], v[162:165], v[178:181], v[60:63]
	s_waitcnt lgkmcnt(3)
	v_mfma_f32_16x16x32_bf16 v[72:75], v[158:161], v[222:225], v[72:75]
	v_mfma_f32_16x16x32_bf16 v[76:79], v[162:165], v[222:225], v[76:79]
	s_waitcnt lgkmcnt(2)
	s_mov_b32 m0, s50
	v_mfma_f32_16x16x32_bf16 v[48:51], v[214:217], v[166:169], v[48:51]
	global_load_lds_dwordx4 v146, s[68:69]
	s_waitcnt lgkmcnt(1)
	v_mfma_f32_16x16x32_bf16 v[174:177], v[218:221], v[166:169], v[174:177]
	ds_read_b128 v[166:169], v28
	v_mfma_f32_16x16x32_bf16 v[64:67], v[214:217], v[178:181], v[64:67]
	v_mfma_f32_16x16x32_bf16 v[170:173], v[218:221], v[178:181], v[170:173]
	ds_read_b128 v[178:181], v29
	v_mfma_f32_16x16x32_bf16 v[80:83], v[214:217], v[222:225], v[80:83]
	v_mfma_f32_16x16x32_bf16 v[32:35], v[218:221], v[222:225], v[32:35]
	ds_read_b128 v[222:225], v30
	s_waitcnt lgkmcnt(3)
	v_mfma_f32_16x16x32_bf16 v[88:91], v[158:161], v[226:229], v[88:91]
	v_mfma_f32_16x16x32_bf16 v[92:95], v[162:165], v[226:229], v[92:95]
	v_mfma_f32_16x16x32_bf16 v[96:99], v[214:217], v[226:229], v[96:99]
	v_mfma_f32_16x16x32_bf16 v[36:39], v[218:221], v[226:229], v[36:39]
	ds_read_b128 v[226:229], v31
	s_waitcnt lgkmcnt(3)
	v_mfma_f32_16x16x32_bf16 v[104:107], v[158:161], v[166:169], v[104:107]
	v_mfma_f32_16x16x32_bf16 v[108:111], v[162:165], v[166:169], v[108:111]
	v_mfma_f32_16x16x32_bf16 v[112:115], v[214:217], v[166:169], v[112:115]
	v_mfma_f32_16x16x32_bf16 v[52:55], v[218:221], v[166:169], v[52:55]
	s_waitcnt lgkmcnt(2)
	v_mfma_f32_16x16x32_bf16 v[116:119], v[158:161], v[178:181], v[116:119]
	v_mfma_f32_16x16x32_bf16 v[120:123], v[162:165], v[178:181], v[120:123]
	v_mfma_f32_16x16x32_bf16 v[124:127], v[214:217], v[178:181], v[124:127]
	v_mfma_f32_16x16x32_bf16 v[68:71], v[218:221], v[178:181], v[68:71]
	s_waitcnt lgkmcnt(1)
	v_mfma_f32_16x16x32_bf16 v[128:131], v[158:161], v[222:225], v[128:131]
	v_mfma_f32_16x16x32_bf16 v[132:135], v[162:165], v[222:225], v[132:135]
	v_mfma_f32_16x16x32_bf16 v[136:139], v[214:217], v[222:225], v[136:139]
	v_mfma_f32_16x16x32_bf16 v[84:87], v[218:221], v[222:225], v[84:87]
	s_waitcnt lgkmcnt(0)
	v_mfma_f32_16x16x32_bf16 v[100:103], v[158:161], v[226:229], v[100:103]
	v_mfma_f32_16x16x32_bf16 v[140:143], v[162:165], v[226:229], v[140:143]
	v_mfma_f32_16x16x32_bf16 v[150:153], v[214:217], v[226:229], v[150:153]
	v_mfma_f32_16x16x32_bf16 v[154:157], v[218:221], v[226:229], v[154:157]
	s_add_u32 s64, s0, 0x1280
	s_addc_u32 s65, s1, 0
	s_add_u32 s68, s14, 0x1280
	s_waitcnt vmcnt(0)
	s_barrier
	s_addc_u32 s69, s15, 0
	ds_read_b128 v[158:161], v7 offset:32768
	ds_read_b128 v[162:165], v6
	ds_read_b128 v[166:169], v7 offset:34816
	ds_read_b128 v[178:181], v6 offset:2048
	ds_read_b128 v[214:217], v7 offset:36864
	ds_read_b128 v[218:221], v7 offset:38912
	ds_read_b128 v[222:225], v6 offset:4096
	ds_read_b128 v[226:229], v6 offset:6144
	s_waitcnt lgkmcnt(6)
	v_mfma_f32_16x16x32_bf16 v[40:43], v[158:161], v[162:165], v[40:43]
	s_waitcnt lgkmcnt(5)
	v_mfma_f32_16x16x32_bf16 v[44:47], v[166:169], v[162:165], v[44:47]
	s_waitcnt lgkmcnt(4)
	v_mfma_f32_16x16x32_bf16 v[56:59], v[158:161], v[178:181], v[56:59]
	s_mov_b32 m0, s52
	v_mfma_f32_16x16x32_bf16 v[60:63], v[166:169], v[178:181], v[60:63]
	global_load_lds_dwordx4 v0, s[64:65]
	s_waitcnt lgkmcnt(3)
	v_mfma_f32_16x16x32_bf16 v[48:51], v[214:217], v[162:165], v[48:51]
	v_mfma_f32_16x16x32_bf16 v[64:67], v[214:217], v[178:181], v[64:67]
	s_waitcnt lgkmcnt(2)
	v_mfma_f32_16x16x32_bf16 v[174:177], v[218:221], v[162:165], v[174:177]
	ds_read_b128 v[162:165], v6 offset:8192
	v_mfma_f32_16x16x32_bf16 v[170:173], v[218:221], v[178:181], v[170:173]
	ds_read_b128 v[178:181], v6 offset:10240
	s_waitcnt lgkmcnt(3)
	s_mov_b32 m0, s51
	v_mfma_f32_16x16x32_bf16 v[72:75], v[158:161], v[222:225], v[72:75]
	global_load_lds_dwordx4 v0, s[68:69]
	v_mfma_f32_16x16x32_bf16 v[76:79], v[166:169], v[222:225], v[76:79]
	v_mfma_f32_16x16x32_bf16 v[80:83], v[214:217], v[222:225], v[80:83]
	v_mfma_f32_16x16x32_bf16 v[32:35], v[218:221], v[222:225], v[32:35]
	ds_read_b128 v[222:225], v6 offset:12288
	s_waitcnt lgkmcnt(3)
	v_mfma_f32_16x16x32_bf16 v[88:91], v[158:161], v[226:229], v[88:91]
	s_mov_b32 m0, s53
	v_mfma_f32_16x16x32_bf16 v[92:95], v[166:169], v[226:229], v[92:95]
	global_load_lds_dwordx4 v2, s[64:65]
	v_mfma_f32_16x16x32_bf16 v[96:99], v[214:217], v[226:229], v[96:99]
	v_mfma_f32_16x16x32_bf16 v[36:39], v[218:221], v[226:229], v[36:39]
	ds_read_b128 v[226:229], v6 offset:14336
	s_waitcnt lgkmcnt(3)
	v_mfma_f32_16x16x32_bf16 v[104:107], v[158:161], v[162:165], v[104:107]
	s_waitcnt lgkmcnt(2)
	v_mfma_f32_16x16x32_bf16 v[116:119], v[158:161], v[178:181], v[116:119]
	s_waitcnt lgkmcnt(1)
	s_mov_b32 m0, s54
	v_mfma_f32_16x16x32_bf16 v[128:131], v[158:161], v[222:225], v[128:131]
	global_load_lds_dwordx4 v2, s[68:69]
	s_waitcnt lgkmcnt(0)
	v_mfma_f32_16x16x32_bf16 v[100:103], v[158:161], v[226:229], v[100:103]
	ds_read_b128 v[158:161], v7 offset:33792
	v_mfma_f32_16x16x32_bf16 v[108:111], v[166:169], v[162:165], v[108:111]
	v_mfma_f32_16x16x32_bf16 v[120:123], v[166:169], v[178:181], v[120:123]
	v_mfma_f32_16x16x32_bf16 v[132:135], v[166:169], v[222:225], v[132:135]
	s_mov_b32 m0, s55
	v_mfma_f32_16x16x32_bf16 v[140:143], v[166:169], v[226:229], v[140:143]
	global_load_lds_dwordx4 v4, s[64:65]
	ds_read_b128 v[166:169], v6 offset:1024
	v_mfma_f32_16x16x32_bf16 v[112:115], v[214:217], v[162:165], v[112:115]
	v_mfma_f32_16x16x32_bf16 v[52:55], v[218:221], v[162:165], v[52:55]
	ds_read_b128 v[162:165], v7 offset:35840
	v_mfma_f32_16x16x32_bf16 v[124:127], v[214:217], v[178:181], v[124:127]
	v_mfma_f32_16x16x32_bf16 v[68:71], v[218:221], v[178:181], v[68:71]
	ds_read_b128 v[178:181], v6 offset:3072
	s_mov_b32 m0, s58
	v_mfma_f32_16x16x32_bf16 v[136:139], v[214:217], v[222:225], v[136:139]
	global_load_lds_dwordx4 v4, s[68:69]
	v_mfma_f32_16x16x32_bf16 v[84:87], v[218:221], v[222:225], v[84:87]
	ds_read_b128 v[222:225], v6 offset:5120
	v_mfma_f32_16x16x32_bf16 v[150:153], v[214:217], v[226:229], v[150:153]
	ds_read_b128 v[214:217], v7 offset:37888
	v_mfma_f32_16x16x32_bf16 v[154:157], v[218:221], v[226:229], v[154:157]
	ds_read_b128 v[218:221], v7 offset:39936
	ds_read_b128 v[226:229], v6 offset:7168
	s_waitcnt lgkmcnt(6)
	v_mfma_f32_16x16x32_bf16 v[40:43], v[158:161], v[166:169], v[40:43]
	s_waitcnt lgkmcnt(5)
	s_mov_b32 m0, s62
	v_mfma_f32_16x16x32_bf16 v[44:47], v[162:165], v[166:169], v[44:47]
	global_load_lds_dwordx4 v146, s[64:65]
	s_waitcnt lgkmcnt(4)
	v_mfma_f32_16x16x32_bf16 v[56:59], v[158:161], v[178:181], v[56:59]
	v_mfma_f32_16x16x32_bf16 v[60:63], v[162:165], v[178:181], v[60:63]
	s_waitcnt lgkmcnt(3)
	v_mfma_f32_16x16x32_bf16 v[72:75], v[158:161], v[222:225], v[72:75]
	v_mfma_f32_16x16x32_bf16 v[76:79], v[162:165], v[222:225], v[76:79]
	s_waitcnt lgkmcnt(2)
	s_mov_b32 m0, s63
	v_mfma_f32_16x16x32_bf16 v[48:51], v[214:217], v[166:169], v[48:51]
	global_load_lds_dwordx4 v146, s[68:69]
	s_waitcnt lgkmcnt(1)
	v_mfma_f32_16x16x32_bf16 v[174:177], v[218:221], v[166:169], v[174:177]
	ds_read_b128 v[166:169], v6 offset:9216
	v_mfma_f32_16x16x32_bf16 v[64:67], v[214:217], v[178:181], v[64:67]
	v_mfma_f32_16x16x32_bf16 v[170:173], v[218:221], v[178:181], v[170:173]
	ds_read_b128 v[178:181], v6 offset:11264
	v_mfma_f32_16x16x32_bf16 v[80:83], v[214:217], v[222:225], v[80:83]
	v_mfma_f32_16x16x32_bf16 v[32:35], v[218:221], v[222:225], v[32:35]
	ds_read_b128 v[222:225], v6 offset:13312
	s_waitcnt lgkmcnt(3)
	v_mfma_f32_16x16x32_bf16 v[88:91], v[158:161], v[226:229], v[88:91]
	v_mfma_f32_16x16x32_bf16 v[92:95], v[162:165], v[226:229], v[92:95]
	v_mfma_f32_16x16x32_bf16 v[96:99], v[214:217], v[226:229], v[96:99]
	v_mfma_f32_16x16x32_bf16 v[36:39], v[218:221], v[226:229], v[36:39]
	ds_read_b128 v[226:229], v6 offset:15360
	s_waitcnt lgkmcnt(3)
	v_mfma_f32_16x16x32_bf16 v[104:107], v[158:161], v[166:169], v[104:107]
	v_mfma_f32_16x16x32_bf16 v[108:111], v[162:165], v[166:169], v[108:111]
	v_mfma_f32_16x16x32_bf16 v[112:115], v[214:217], v[166:169], v[112:115]
	v_mfma_f32_16x16x32_bf16 v[52:55], v[218:221], v[166:169], v[52:55]
	s_waitcnt lgkmcnt(2)
	v_mfma_f32_16x16x32_bf16 v[116:119], v[158:161], v[178:181], v[116:119]
	v_mfma_f32_16x16x32_bf16 v[120:123], v[162:165], v[178:181], v[120:123]
	v_mfma_f32_16x16x32_bf16 v[124:127], v[214:217], v[178:181], v[124:127]
	v_mfma_f32_16x16x32_bf16 v[68:71], v[218:221], v[178:181], v[68:71]
	s_waitcnt lgkmcnt(1)
	v_mfma_f32_16x16x32_bf16 v[128:131], v[158:161], v[222:225], v[128:131]
	v_mfma_f32_16x16x32_bf16 v[132:135], v[162:165], v[222:225], v[132:135]
	v_mfma_f32_16x16x32_bf16 v[136:139], v[214:217], v[222:225], v[136:139]
	v_mfma_f32_16x16x32_bf16 v[84:87], v[218:221], v[222:225], v[84:87]
	s_waitcnt lgkmcnt(0)
	v_mfma_f32_16x16x32_bf16 v[100:103], v[158:161], v[226:229], v[100:103]
	v_mfma_f32_16x16x32_bf16 v[140:143], v[162:165], v[226:229], v[140:143]
	v_mfma_f32_16x16x32_bf16 v[150:153], v[214:217], v[226:229], v[150:153]
	v_mfma_f32_16x16x32_bf16 v[154:157], v[218:221], v[226:229], v[154:157]
	s_add_u32 s64, s0, 0x1300
	s_addc_u32 s65, s1, 0
	s_add_u32 s68, s14, 0x1300
	s_waitcnt vmcnt(0)
	s_barrier
	s_addc_u32 s69, s15, 0
	ds_read_b128 v[158:161], v8
	ds_read_b128 v[162:165], v12
	ds_read_b128 v[166:169], v9
	ds_read_b128 v[178:181], v13
	ds_read_b128 v[214:217], v11
	ds_read_b128 v[218:221], v10
	ds_read_b128 v[222:225], v14
	ds_read_b128 v[226:229], v15
	s_waitcnt lgkmcnt(6)
	v_mfma_f32_16x16x32_bf16 v[40:43], v[158:161], v[162:165], v[40:43]
	s_waitcnt lgkmcnt(5)
	v_mfma_f32_16x16x32_bf16 v[44:47], v[166:169], v[162:165], v[44:47]
	s_waitcnt lgkmcnt(4)
	v_mfma_f32_16x16x32_bf16 v[56:59], v[158:161], v[178:181], v[56:59]
	s_mov_b32 m0, s42
	v_mfma_f32_16x16x32_bf16 v[60:63], v[166:169], v[178:181], v[60:63]
	global_load_lds_dwordx4 v0, s[64:65]
	s_waitcnt lgkmcnt(3)
	v_mfma_f32_16x16x32_bf16 v[48:51], v[214:217], v[162:165], v[48:51]
	v_mfma_f32_16x16x32_bf16 v[64:67], v[214:217], v[178:181], v[64:67]
	s_waitcnt lgkmcnt(2)
	v_mfma_f32_16x16x32_bf16 v[174:177], v[218:221], v[162:165], v[174:177]
	ds_read_b128 v[162:165], v16
	v_mfma_f32_16x16x32_bf16 v[170:173], v[218:221], v[178:181], v[170:173]
	ds_read_b128 v[178:181], v17
	s_waitcnt lgkmcnt(3)
	s_mov_b32 m0, s43
	v_mfma_f32_16x16x32_bf16 v[72:75], v[158:161], v[222:225], v[72:75]
	global_load_lds_dwordx4 v0, s[68:69]
	v_mfma_f32_16x16x32_bf16 v[76:79], v[166:169], v[222:225], v[76:79]
	v_mfma_f32_16x16x32_bf16 v[80:83], v[214:217], v[222:225], v[80:83]
	v_mfma_f32_16x16x32_bf16 v[32:35], v[218:221], v[222:225], v[32:35]
	ds_read_b128 v[222:225], v18
	s_waitcnt lgkmcnt(3)
	v_mfma_f32_16x16x32_bf16 v[88:91], v[158:161], v[226:229], v[88:91]
	s_mov_b32 m0, s44
	v_mfma_f32_16x16x32_bf16 v[92:95], v[166:169], v[226:229], v[92:95]
	global_load_lds_dwordx4 v2, s[64:65]
	v_mfma_f32_16x16x32_bf16 v[96:99], v[214:217], v[226:229], v[96:99]
	v_mfma_f32_16x16x32_bf16 v[36:39], v[218:221], v[226:229], v[36:39]
	ds_read_b128 v[226:229], v19
	s_waitcnt lgkmcnt(3)
	v_mfma_f32_16x16x32_bf16 v[104:107], v[158:161], v[162:165], v[104:107]
	s_waitcnt lgkmcnt(2)
	v_mfma_f32_16x16x32_bf16 v[116:119], v[158:161], v[178:181], v[116:119]
	s_waitcnt lgkmcnt(1)
	s_mov_b32 m0, s45
	v_mfma_f32_16x16x32_bf16 v[128:131], v[158:161], v[222:225], v[128:131]
	global_load_lds_dwordx4 v2, s[68:69]
	s_waitcnt lgkmcnt(0)
	v_mfma_f32_16x16x32_bf16 v[100:103], v[158:161], v[226:229], v[100:103]
	ds_read_b128 v[158:161], v20
	v_mfma_f32_16x16x32_bf16 v[108:111], v[166:169], v[162:165], v[108:111]
	v_mfma_f32_16x16x32_bf16 v[120:123], v[166:169], v[178:181], v[120:123]
	v_mfma_f32_16x16x32_bf16 v[132:135], v[166:169], v[222:225], v[132:135]
	s_mov_b32 m0, s46
	v_mfma_f32_16x16x32_bf16 v[140:143], v[166:169], v[226:229], v[140:143]
	global_load_lds_dwordx4 v4, s[64:65]
	ds_read_b128 v[166:169], v24
	v_mfma_f32_16x16x32_bf16 v[112:115], v[214:217], v[162:165], v[112:115]
	v_mfma_f32_16x16x32_bf16 v[52:55], v[218:221], v[162:165], v[52:55]
	ds_read_b128 v[162:165], v21
	v_mfma_f32_16x16x32_bf16 v[124:127], v[214:217], v[178:181], v[124:127]
	v_mfma_f32_16x16x32_bf16 v[68:71], v[218:221], v[178:181], v[68:71]
	ds_read_b128 v[178:181], v25
	s_mov_b32 m0, s47
	v_mfma_f32_16x16x32_bf16 v[136:139], v[214:217], v[222:225], v[136:139]
	global_load_lds_dwordx4 v4, s[68:69]
	v_mfma_f32_16x16x32_bf16 v[84:87], v[218:221], v[222:225], v[84:87]
	ds_read_b128 v[222:225], v26
	v_mfma_f32_16x16x32_bf16 v[150:153], v[214:217], v[226:229], v[150:153]
	ds_read_b128 v[214:217], v23
	v_mfma_f32_16x16x32_bf16 v[154:157], v[218:221], v[226:229], v[154:157]
	ds_read_b128 v[218:221], v22
	ds_read_b128 v[226:229], v27
	s_waitcnt lgkmcnt(6)
	v_mfma_f32_16x16x32_bf16 v[40:43], v[158:161], v[166:169], v[40:43]
	s_waitcnt lgkmcnt(5)
	s_mov_b32 m0, s49
	v_mfma_f32_16x16x32_bf16 v[44:47], v[162:165], v[166:169], v[44:47]
	global_load_lds_dwordx4 v146, s[64:65]
	s_waitcnt lgkmcnt(4)
	v_mfma_f32_16x16x32_bf16 v[56:59], v[158:161], v[178:181], v[56:59]
	v_mfma_f32_16x16x32_bf16 v[60:63], v[162:165], v[178:181], v[60:63]
	s_waitcnt lgkmcnt(3)
	v_mfma_f32_16x16x32_bf16 v[72:75], v[158:161], v[222:225], v[72:75]
	v_mfma_f32_16x16x32_bf16 v[76:79], v[162:165], v[222:225], v[76:79]
	s_waitcnt lgkmcnt(2)
	s_mov_b32 m0, s50
	v_mfma_f32_16x16x32_bf16 v[48:51], v[214:217], v[166:169], v[48:51]
	global_load_lds_dwordx4 v146, s[68:69]
	s_waitcnt lgkmcnt(1)
	v_mfma_f32_16x16x32_bf16 v[174:177], v[218:221], v[166:169], v[174:177]
	ds_read_b128 v[166:169], v28
	v_mfma_f32_16x16x32_bf16 v[64:67], v[214:217], v[178:181], v[64:67]
	v_mfma_f32_16x16x32_bf16 v[170:173], v[218:221], v[178:181], v[170:173]
	ds_read_b128 v[178:181], v29
	v_mfma_f32_16x16x32_bf16 v[80:83], v[214:217], v[222:225], v[80:83]
	v_mfma_f32_16x16x32_bf16 v[32:35], v[218:221], v[222:225], v[32:35]
	ds_read_b128 v[222:225], v30
	s_waitcnt lgkmcnt(3)
	v_mfma_f32_16x16x32_bf16 v[88:91], v[158:161], v[226:229], v[88:91]
	v_mfma_f32_16x16x32_bf16 v[92:95], v[162:165], v[226:229], v[92:95]
	v_mfma_f32_16x16x32_bf16 v[96:99], v[214:217], v[226:229], v[96:99]
	v_mfma_f32_16x16x32_bf16 v[36:39], v[218:221], v[226:229], v[36:39]
	ds_read_b128 v[226:229], v31
	s_waitcnt lgkmcnt(3)
	v_mfma_f32_16x16x32_bf16 v[104:107], v[158:161], v[166:169], v[104:107]
	v_mfma_f32_16x16x32_bf16 v[108:111], v[162:165], v[166:169], v[108:111]
	v_mfma_f32_16x16x32_bf16 v[112:115], v[214:217], v[166:169], v[112:115]
	v_mfma_f32_16x16x32_bf16 v[52:55], v[218:221], v[166:169], v[52:55]
	s_waitcnt lgkmcnt(2)
	v_mfma_f32_16x16x32_bf16 v[116:119], v[158:161], v[178:181], v[116:119]
	v_mfma_f32_16x16x32_bf16 v[120:123], v[162:165], v[178:181], v[120:123]
	v_mfma_f32_16x16x32_bf16 v[124:127], v[214:217], v[178:181], v[124:127]
	v_mfma_f32_16x16x32_bf16 v[68:71], v[218:221], v[178:181], v[68:71]
	s_waitcnt lgkmcnt(1)
	v_mfma_f32_16x16x32_bf16 v[128:131], v[158:161], v[222:225], v[128:131]
	v_mfma_f32_16x16x32_bf16 v[132:135], v[162:165], v[222:225], v[132:135]
	v_mfma_f32_16x16x32_bf16 v[136:139], v[214:217], v[222:225], v[136:139]
	v_mfma_f32_16x16x32_bf16 v[84:87], v[218:221], v[222:225], v[84:87]
	s_waitcnt lgkmcnt(0)
	v_mfma_f32_16x16x32_bf16 v[100:103], v[158:161], v[226:229], v[100:103]
	v_mfma_f32_16x16x32_bf16 v[140:143], v[162:165], v[226:229], v[140:143]
	v_mfma_f32_16x16x32_bf16 v[150:153], v[214:217], v[226:229], v[150:153]
	v_mfma_f32_16x16x32_bf16 v[154:157], v[218:221], v[226:229], v[154:157]
	s_add_u32 s64, s0, 0x1380
	s_addc_u32 s65, s1, 0
	s_add_u32 s68, s14, 0x1380
	s_waitcnt vmcnt(0)
	s_barrier
	s_addc_u32 s69, s15, 0
	ds_read_b128 v[158:161], v7 offset:32768
	ds_read_b128 v[162:165], v6
	ds_read_b128 v[166:169], v7 offset:34816
	ds_read_b128 v[178:181], v6 offset:2048
	ds_read_b128 v[214:217], v7 offset:36864
	ds_read_b128 v[218:221], v7 offset:38912
	ds_read_b128 v[222:225], v6 offset:4096
	ds_read_b128 v[226:229], v6 offset:6144
	s_waitcnt lgkmcnt(6)
	v_mfma_f32_16x16x32_bf16 v[40:43], v[158:161], v[162:165], v[40:43]
	s_waitcnt lgkmcnt(5)
	v_mfma_f32_16x16x32_bf16 v[44:47], v[166:169], v[162:165], v[44:47]
	s_waitcnt lgkmcnt(4)
	v_mfma_f32_16x16x32_bf16 v[56:59], v[158:161], v[178:181], v[56:59]
	s_mov_b32 m0, s52
	v_mfma_f32_16x16x32_bf16 v[60:63], v[166:169], v[178:181], v[60:63]
	global_load_lds_dwordx4 v0, s[64:65]
	s_waitcnt lgkmcnt(3)
	v_mfma_f32_16x16x32_bf16 v[48:51], v[214:217], v[162:165], v[48:51]
	v_mfma_f32_16x16x32_bf16 v[64:67], v[214:217], v[178:181], v[64:67]
	s_waitcnt lgkmcnt(2)
	v_mfma_f32_16x16x32_bf16 v[174:177], v[218:221], v[162:165], v[174:177]
	ds_read_b128 v[162:165], v6 offset:8192
	v_mfma_f32_16x16x32_bf16 v[170:173], v[218:221], v[178:181], v[170:173]
	ds_read_b128 v[178:181], v6 offset:10240
	s_waitcnt lgkmcnt(3)
	s_mov_b32 m0, s51
	v_mfma_f32_16x16x32_bf16 v[72:75], v[158:161], v[222:225], v[72:75]
	global_load_lds_dwordx4 v0, s[68:69]
	v_mfma_f32_16x16x32_bf16 v[76:79], v[166:169], v[222:225], v[76:79]
	v_mfma_f32_16x16x32_bf16 v[80:83], v[214:217], v[222:225], v[80:83]
	v_mfma_f32_16x16x32_bf16 v[32:35], v[218:221], v[222:225], v[32:35]
	ds_read_b128 v[222:225], v6 offset:12288
	s_waitcnt lgkmcnt(3)
	v_mfma_f32_16x16x32_bf16 v[88:91], v[158:161], v[226:229], v[88:91]
	s_mov_b32 m0, s53
	v_mfma_f32_16x16x32_bf16 v[92:95], v[166:169], v[226:229], v[92:95]
	global_load_lds_dwordx4 v2, s[64:65]
	v_mfma_f32_16x16x32_bf16 v[96:99], v[214:217], v[226:229], v[96:99]
	v_mfma_f32_16x16x32_bf16 v[36:39], v[218:221], v[226:229], v[36:39]
	ds_read_b128 v[226:229], v6 offset:14336
	s_waitcnt lgkmcnt(3)
	v_mfma_f32_16x16x32_bf16 v[104:107], v[158:161], v[162:165], v[104:107]
	s_waitcnt lgkmcnt(2)
	v_mfma_f32_16x16x32_bf16 v[116:119], v[158:161], v[178:181], v[116:119]
	s_waitcnt lgkmcnt(1)
	s_mov_b32 m0, s54
	v_mfma_f32_16x16x32_bf16 v[128:131], v[158:161], v[222:225], v[128:131]
	global_load_lds_dwordx4 v2, s[68:69]
	s_waitcnt lgkmcnt(0)
	v_mfma_f32_16x16x32_bf16 v[100:103], v[158:161], v[226:229], v[100:103]
	ds_read_b128 v[158:161], v7 offset:33792
	v_mfma_f32_16x16x32_bf16 v[108:111], v[166:169], v[162:165], v[108:111]
	v_mfma_f32_16x16x32_bf16 v[120:123], v[166:169], v[178:181], v[120:123]
	v_mfma_f32_16x16x32_bf16 v[132:135], v[166:169], v[222:225], v[132:135]
	s_mov_b32 m0, s55
	v_mfma_f32_16x16x32_bf16 v[140:143], v[166:169], v[226:229], v[140:143]
	global_load_lds_dwordx4 v4, s[64:65]
	ds_read_b128 v[166:169], v6 offset:1024
	v_mfma_f32_16x16x32_bf16 v[112:115], v[214:217], v[162:165], v[112:115]
	v_mfma_f32_16x16x32_bf16 v[52:55], v[218:221], v[162:165], v[52:55]
	ds_read_b128 v[162:165], v7 offset:35840
	v_mfma_f32_16x16x32_bf16 v[124:127], v[214:217], v[178:181], v[124:127]
	v_mfma_f32_16x16x32_bf16 v[68:71], v[218:221], v[178:181], v[68:71]
	ds_read_b128 v[178:181], v6 offset:3072
	s_mov_b32 m0, s58
	v_mfma_f32_16x16x32_bf16 v[136:139], v[214:217], v[222:225], v[136:139]
	global_load_lds_dwordx4 v4, s[68:69]
	v_mfma_f32_16x16x32_bf16 v[84:87], v[218:221], v[222:225], v[84:87]
	ds_read_b128 v[222:225], v6 offset:5120
	v_mfma_f32_16x16x32_bf16 v[150:153], v[214:217], v[226:229], v[150:153]
	ds_read_b128 v[214:217], v7 offset:37888
	v_mfma_f32_16x16x32_bf16 v[154:157], v[218:221], v[226:229], v[154:157]
	ds_read_b128 v[218:221], v7 offset:39936
	ds_read_b128 v[226:229], v6 offset:7168
	s_waitcnt lgkmcnt(6)
	v_mfma_f32_16x16x32_bf16 v[40:43], v[158:161], v[166:169], v[40:43]
	s_waitcnt lgkmcnt(5)
	s_mov_b32 m0, s62
	v_mfma_f32_16x16x32_bf16 v[44:47], v[162:165], v[166:169], v[44:47]
	global_load_lds_dwordx4 v146, s[64:65]
	s_waitcnt lgkmcnt(4)
	v_mfma_f32_16x16x32_bf16 v[56:59], v[158:161], v[178:181], v[56:59]
	v_mfma_f32_16x16x32_bf16 v[60:63], v[162:165], v[178:181], v[60:63]
	s_waitcnt lgkmcnt(3)
	v_mfma_f32_16x16x32_bf16 v[72:75], v[158:161], v[222:225], v[72:75]
	v_mfma_f32_16x16x32_bf16 v[76:79], v[162:165], v[222:225], v[76:79]
	s_waitcnt lgkmcnt(2)
	s_mov_b32 m0, s63
	v_mfma_f32_16x16x32_bf16 v[48:51], v[214:217], v[166:169], v[48:51]
	global_load_lds_dwordx4 v146, s[68:69]
	s_waitcnt lgkmcnt(1)
	v_mfma_f32_16x16x32_bf16 v[174:177], v[218:221], v[166:169], v[174:177]
	ds_read_b128 v[166:169], v6 offset:9216
	v_mfma_f32_16x16x32_bf16 v[64:67], v[214:217], v[178:181], v[64:67]
	v_mfma_f32_16x16x32_bf16 v[170:173], v[218:221], v[178:181], v[170:173]
	ds_read_b128 v[178:181], v6 offset:11264
	v_mfma_f32_16x16x32_bf16 v[80:83], v[214:217], v[222:225], v[80:83]
	v_mfma_f32_16x16x32_bf16 v[32:35], v[218:221], v[222:225], v[32:35]
	ds_read_b128 v[222:225], v6 offset:13312
	s_waitcnt lgkmcnt(3)
	v_mfma_f32_16x16x32_bf16 v[88:91], v[158:161], v[226:229], v[88:91]
	v_mfma_f32_16x16x32_bf16 v[92:95], v[162:165], v[226:229], v[92:95]
	v_mfma_f32_16x16x32_bf16 v[96:99], v[214:217], v[226:229], v[96:99]
	v_mfma_f32_16x16x32_bf16 v[36:39], v[218:221], v[226:229], v[36:39]
	ds_read_b128 v[226:229], v6 offset:15360
	s_waitcnt lgkmcnt(3)
	v_mfma_f32_16x16x32_bf16 v[104:107], v[158:161], v[166:169], v[104:107]
	v_mfma_f32_16x16x32_bf16 v[108:111], v[162:165], v[166:169], v[108:111]
	v_mfma_f32_16x16x32_bf16 v[112:115], v[214:217], v[166:169], v[112:115]
	v_mfma_f32_16x16x32_bf16 v[52:55], v[218:221], v[166:169], v[52:55]
	s_waitcnt lgkmcnt(2)
	v_mfma_f32_16x16x32_bf16 v[116:119], v[158:161], v[178:181], v[116:119]
	v_mfma_f32_16x16x32_bf16 v[120:123], v[162:165], v[178:181], v[120:123]
	v_mfma_f32_16x16x32_bf16 v[124:127], v[214:217], v[178:181], v[124:127]
	v_mfma_f32_16x16x32_bf16 v[68:71], v[218:221], v[178:181], v[68:71]
	s_waitcnt lgkmcnt(1)
	v_mfma_f32_16x16x32_bf16 v[128:131], v[158:161], v[222:225], v[128:131]
	v_mfma_f32_16x16x32_bf16 v[132:135], v[162:165], v[222:225], v[132:135]
	v_mfma_f32_16x16x32_bf16 v[136:139], v[214:217], v[222:225], v[136:139]
	v_mfma_f32_16x16x32_bf16 v[84:87], v[218:221], v[222:225], v[84:87]
	s_waitcnt lgkmcnt(0)
	v_mfma_f32_16x16x32_bf16 v[100:103], v[158:161], v[226:229], v[100:103]
	v_mfma_f32_16x16x32_bf16 v[140:143], v[162:165], v[226:229], v[140:143]
	v_mfma_f32_16x16x32_bf16 v[150:153], v[214:217], v[226:229], v[150:153]
	v_mfma_f32_16x16x32_bf16 v[154:157], v[218:221], v[226:229], v[154:157]
	s_add_u32 s64, s0, 0x1400
	s_addc_u32 s65, s1, 0
	s_add_u32 s68, s14, 0x1400
	s_waitcnt vmcnt(0)
	s_barrier
	s_addc_u32 s69, s15, 0
	ds_read_b128 v[158:161], v8
	ds_read_b128 v[162:165], v12
	ds_read_b128 v[166:169], v9
	ds_read_b128 v[178:181], v13
	ds_read_b128 v[214:217], v11
	ds_read_b128 v[218:221], v10
	ds_read_b128 v[222:225], v14
	ds_read_b128 v[226:229], v15
	s_waitcnt lgkmcnt(6)
	v_mfma_f32_16x16x32_bf16 v[40:43], v[158:161], v[162:165], v[40:43]
	s_waitcnt lgkmcnt(5)
	v_mfma_f32_16x16x32_bf16 v[44:47], v[166:169], v[162:165], v[44:47]
	s_waitcnt lgkmcnt(4)
	v_mfma_f32_16x16x32_bf16 v[56:59], v[158:161], v[178:181], v[56:59]
	s_mov_b32 m0, s42
	v_mfma_f32_16x16x32_bf16 v[60:63], v[166:169], v[178:181], v[60:63]
	global_load_lds_dwordx4 v0, s[64:65]
	s_waitcnt lgkmcnt(3)
	v_mfma_f32_16x16x32_bf16 v[48:51], v[214:217], v[162:165], v[48:51]
	v_mfma_f32_16x16x32_bf16 v[64:67], v[214:217], v[178:181], v[64:67]
	s_waitcnt lgkmcnt(2)
	v_mfma_f32_16x16x32_bf16 v[174:177], v[218:221], v[162:165], v[174:177]
	ds_read_b128 v[162:165], v16
	v_mfma_f32_16x16x32_bf16 v[170:173], v[218:221], v[178:181], v[170:173]
	ds_read_b128 v[178:181], v17
	s_waitcnt lgkmcnt(3)
	s_mov_b32 m0, s43
	v_mfma_f32_16x16x32_bf16 v[72:75], v[158:161], v[222:225], v[72:75]
	global_load_lds_dwordx4 v0, s[68:69]
	v_mfma_f32_16x16x32_bf16 v[76:79], v[166:169], v[222:225], v[76:79]
	v_mfma_f32_16x16x32_bf16 v[80:83], v[214:217], v[222:225], v[80:83]
	v_mfma_f32_16x16x32_bf16 v[32:35], v[218:221], v[222:225], v[32:35]
	ds_read_b128 v[222:225], v18
	s_waitcnt lgkmcnt(3)
	v_mfma_f32_16x16x32_bf16 v[88:91], v[158:161], v[226:229], v[88:91]
	s_mov_b32 m0, s44
	v_mfma_f32_16x16x32_bf16 v[92:95], v[166:169], v[226:229], v[92:95]
	global_load_lds_dwordx4 v2, s[64:65]
	v_mfma_f32_16x16x32_bf16 v[96:99], v[214:217], v[226:229], v[96:99]
	v_mfma_f32_16x16x32_bf16 v[36:39], v[218:221], v[226:229], v[36:39]
	ds_read_b128 v[226:229], v19
	s_waitcnt lgkmcnt(3)
	v_mfma_f32_16x16x32_bf16 v[104:107], v[158:161], v[162:165], v[104:107]
	s_waitcnt lgkmcnt(2)
	v_mfma_f32_16x16x32_bf16 v[116:119], v[158:161], v[178:181], v[116:119]
	s_waitcnt lgkmcnt(1)
	s_mov_b32 m0, s45
	v_mfma_f32_16x16x32_bf16 v[128:131], v[158:161], v[222:225], v[128:131]
	global_load_lds_dwordx4 v2, s[68:69]
	s_waitcnt lgkmcnt(0)
	v_mfma_f32_16x16x32_bf16 v[100:103], v[158:161], v[226:229], v[100:103]
	ds_read_b128 v[158:161], v20
	v_mfma_f32_16x16x32_bf16 v[108:111], v[166:169], v[162:165], v[108:111]
	v_mfma_f32_16x16x32_bf16 v[120:123], v[166:169], v[178:181], v[120:123]
	v_mfma_f32_16x16x32_bf16 v[132:135], v[166:169], v[222:225], v[132:135]
	s_mov_b32 m0, s46
	v_mfma_f32_16x16x32_bf16 v[140:143], v[166:169], v[226:229], v[140:143]
	global_load_lds_dwordx4 v4, s[64:65]
	ds_read_b128 v[166:169], v24
	v_mfma_f32_16x16x32_bf16 v[112:115], v[214:217], v[162:165], v[112:115]
	v_mfma_f32_16x16x32_bf16 v[52:55], v[218:221], v[162:165], v[52:55]
	ds_read_b128 v[162:165], v21
	v_mfma_f32_16x16x32_bf16 v[124:127], v[214:217], v[178:181], v[124:127]
	v_mfma_f32_16x16x32_bf16 v[68:71], v[218:221], v[178:181], v[68:71]
	ds_read_b128 v[178:181], v25
	s_mov_b32 m0, s47
	v_mfma_f32_16x16x32_bf16 v[136:139], v[214:217], v[222:225], v[136:139]
	global_load_lds_dwordx4 v4, s[68:69]
	v_mfma_f32_16x16x32_bf16 v[84:87], v[218:221], v[222:225], v[84:87]
	ds_read_b128 v[222:225], v26
	v_mfma_f32_16x16x32_bf16 v[150:153], v[214:217], v[226:229], v[150:153]
	ds_read_b128 v[214:217], v23
	v_mfma_f32_16x16x32_bf16 v[154:157], v[218:221], v[226:229], v[154:157]
	ds_read_b128 v[218:221], v22
	ds_read_b128 v[226:229], v27
	s_waitcnt lgkmcnt(6)
	v_mfma_f32_16x16x32_bf16 v[40:43], v[158:161], v[166:169], v[40:43]
	s_waitcnt lgkmcnt(5)
	s_mov_b32 m0, s49
	v_mfma_f32_16x16x32_bf16 v[44:47], v[162:165], v[166:169], v[44:47]
	global_load_lds_dwordx4 v146, s[64:65]
	s_waitcnt lgkmcnt(4)
	v_mfma_f32_16x16x32_bf16 v[56:59], v[158:161], v[178:181], v[56:59]
	v_mfma_f32_16x16x32_bf16 v[60:63], v[162:165], v[178:181], v[60:63]
	s_waitcnt lgkmcnt(3)
	v_mfma_f32_16x16x32_bf16 v[72:75], v[158:161], v[222:225], v[72:75]
	v_mfma_f32_16x16x32_bf16 v[76:79], v[162:165], v[222:225], v[76:79]
	s_waitcnt lgkmcnt(2)
	s_mov_b32 m0, s50
	v_mfma_f32_16x16x32_bf16 v[48:51], v[214:217], v[166:169], v[48:51]
	global_load_lds_dwordx4 v146, s[68:69]
	s_waitcnt lgkmcnt(1)
	v_mfma_f32_16x16x32_bf16 v[174:177], v[218:221], v[166:169], v[174:177]
	ds_read_b128 v[166:169], v28
	v_mfma_f32_16x16x32_bf16 v[64:67], v[214:217], v[178:181], v[64:67]
	v_mfma_f32_16x16x32_bf16 v[170:173], v[218:221], v[178:181], v[170:173]
	ds_read_b128 v[178:181], v29
	v_mfma_f32_16x16x32_bf16 v[80:83], v[214:217], v[222:225], v[80:83]
	v_mfma_f32_16x16x32_bf16 v[32:35], v[218:221], v[222:225], v[32:35]
	ds_read_b128 v[222:225], v30
	s_waitcnt lgkmcnt(3)
	v_mfma_f32_16x16x32_bf16 v[88:91], v[158:161], v[226:229], v[88:91]
	v_mfma_f32_16x16x32_bf16 v[92:95], v[162:165], v[226:229], v[92:95]
	v_mfma_f32_16x16x32_bf16 v[96:99], v[214:217], v[226:229], v[96:99]
	v_mfma_f32_16x16x32_bf16 v[36:39], v[218:221], v[226:229], v[36:39]
	ds_read_b128 v[226:229], v31
	s_waitcnt lgkmcnt(3)
	v_mfma_f32_16x16x32_bf16 v[104:107], v[158:161], v[166:169], v[104:107]
	v_mfma_f32_16x16x32_bf16 v[108:111], v[162:165], v[166:169], v[108:111]
	v_mfma_f32_16x16x32_bf16 v[112:115], v[214:217], v[166:169], v[112:115]
	v_mfma_f32_16x16x32_bf16 v[52:55], v[218:221], v[166:169], v[52:55]
	s_waitcnt lgkmcnt(2)
	v_mfma_f32_16x16x32_bf16 v[116:119], v[158:161], v[178:181], v[116:119]
	v_mfma_f32_16x16x32_bf16 v[120:123], v[162:165], v[178:181], v[120:123]
	v_mfma_f32_16x16x32_bf16 v[124:127], v[214:217], v[178:181], v[124:127]
	v_mfma_f32_16x16x32_bf16 v[68:71], v[218:221], v[178:181], v[68:71]
	s_waitcnt lgkmcnt(1)
	v_mfma_f32_16x16x32_bf16 v[128:131], v[158:161], v[222:225], v[128:131]
	v_mfma_f32_16x16x32_bf16 v[132:135], v[162:165], v[222:225], v[132:135]
	v_mfma_f32_16x16x32_bf16 v[136:139], v[214:217], v[222:225], v[136:139]
	v_mfma_f32_16x16x32_bf16 v[84:87], v[218:221], v[222:225], v[84:87]
	s_waitcnt lgkmcnt(0)
	v_mfma_f32_16x16x32_bf16 v[100:103], v[158:161], v[226:229], v[100:103]
	v_mfma_f32_16x16x32_bf16 v[140:143], v[162:165], v[226:229], v[140:143]
	v_mfma_f32_16x16x32_bf16 v[150:153], v[214:217], v[226:229], v[150:153]
	v_mfma_f32_16x16x32_bf16 v[154:157], v[218:221], v[226:229], v[154:157]
	s_add_u32 s64, s0, 0x1480
	s_addc_u32 s65, s1, 0
	s_add_u32 s68, s14, 0x1480
	s_waitcnt vmcnt(0)
	s_barrier
	s_addc_u32 s69, s15, 0
	ds_read_b128 v[158:161], v7 offset:32768
	ds_read_b128 v[162:165], v6
	ds_read_b128 v[166:169], v7 offset:34816
	ds_read_b128 v[178:181], v6 offset:2048
	ds_read_b128 v[214:217], v7 offset:36864
	ds_read_b128 v[218:221], v7 offset:38912
	ds_read_b128 v[222:225], v6 offset:4096
	ds_read_b128 v[226:229], v6 offset:6144
	s_waitcnt lgkmcnt(6)
	v_mfma_f32_16x16x32_bf16 v[40:43], v[158:161], v[162:165], v[40:43]
	s_waitcnt lgkmcnt(5)
	v_mfma_f32_16x16x32_bf16 v[44:47], v[166:169], v[162:165], v[44:47]
	s_waitcnt lgkmcnt(4)
	v_mfma_f32_16x16x32_bf16 v[56:59], v[158:161], v[178:181], v[56:59]
	s_mov_b32 m0, s52
	v_mfma_f32_16x16x32_bf16 v[60:63], v[166:169], v[178:181], v[60:63]
	global_load_lds_dwordx4 v0, s[64:65]
	s_waitcnt lgkmcnt(3)
	v_mfma_f32_16x16x32_bf16 v[48:51], v[214:217], v[162:165], v[48:51]
	v_mfma_f32_16x16x32_bf16 v[64:67], v[214:217], v[178:181], v[64:67]
	s_waitcnt lgkmcnt(2)
	v_mfma_f32_16x16x32_bf16 v[174:177], v[218:221], v[162:165], v[174:177]
	ds_read_b128 v[162:165], v6 offset:8192
	v_mfma_f32_16x16x32_bf16 v[170:173], v[218:221], v[178:181], v[170:173]
	ds_read_b128 v[178:181], v6 offset:10240
	s_waitcnt lgkmcnt(3)
	s_mov_b32 m0, s51
	v_mfma_f32_16x16x32_bf16 v[72:75], v[158:161], v[222:225], v[72:75]
	global_load_lds_dwordx4 v0, s[68:69]
	v_mfma_f32_16x16x32_bf16 v[76:79], v[166:169], v[222:225], v[76:79]
	v_mfma_f32_16x16x32_bf16 v[80:83], v[214:217], v[222:225], v[80:83]
	v_mfma_f32_16x16x32_bf16 v[32:35], v[218:221], v[222:225], v[32:35]
	ds_read_b128 v[222:225], v6 offset:12288
	s_waitcnt lgkmcnt(3)
	v_mfma_f32_16x16x32_bf16 v[88:91], v[158:161], v[226:229], v[88:91]
	s_mov_b32 m0, s53
	v_mfma_f32_16x16x32_bf16 v[92:95], v[166:169], v[226:229], v[92:95]
	global_load_lds_dwordx4 v2, s[64:65]
	v_mfma_f32_16x16x32_bf16 v[96:99], v[214:217], v[226:229], v[96:99]
	v_mfma_f32_16x16x32_bf16 v[36:39], v[218:221], v[226:229], v[36:39]
	ds_read_b128 v[226:229], v6 offset:14336
	s_waitcnt lgkmcnt(3)
	v_mfma_f32_16x16x32_bf16 v[104:107], v[158:161], v[162:165], v[104:107]
	s_waitcnt lgkmcnt(2)
	v_mfma_f32_16x16x32_bf16 v[116:119], v[158:161], v[178:181], v[116:119]
	s_waitcnt lgkmcnt(1)
	s_mov_b32 m0, s54
	v_mfma_f32_16x16x32_bf16 v[128:131], v[158:161], v[222:225], v[128:131]
	global_load_lds_dwordx4 v2, s[68:69]
	s_waitcnt lgkmcnt(0)
	v_mfma_f32_16x16x32_bf16 v[100:103], v[158:161], v[226:229], v[100:103]
	ds_read_b128 v[158:161], v7 offset:33792
	v_mfma_f32_16x16x32_bf16 v[108:111], v[166:169], v[162:165], v[108:111]
	v_mfma_f32_16x16x32_bf16 v[120:123], v[166:169], v[178:181], v[120:123]
	v_mfma_f32_16x16x32_bf16 v[132:135], v[166:169], v[222:225], v[132:135]
	s_mov_b32 m0, s55
	v_mfma_f32_16x16x32_bf16 v[140:143], v[166:169], v[226:229], v[140:143]
	global_load_lds_dwordx4 v4, s[64:65]
	ds_read_b128 v[166:169], v6 offset:1024
	v_mfma_f32_16x16x32_bf16 v[112:115], v[214:217], v[162:165], v[112:115]
	v_mfma_f32_16x16x32_bf16 v[52:55], v[218:221], v[162:165], v[52:55]
	ds_read_b128 v[162:165], v7 offset:35840
	v_mfma_f32_16x16x32_bf16 v[124:127], v[214:217], v[178:181], v[124:127]
	v_mfma_f32_16x16x32_bf16 v[68:71], v[218:221], v[178:181], v[68:71]
	ds_read_b128 v[178:181], v6 offset:3072
	s_mov_b32 m0, s58
	v_mfma_f32_16x16x32_bf16 v[136:139], v[214:217], v[222:225], v[136:139]
	global_load_lds_dwordx4 v4, s[68:69]
	v_mfma_f32_16x16x32_bf16 v[84:87], v[218:221], v[222:225], v[84:87]
	ds_read_b128 v[222:225], v6 offset:5120
	v_mfma_f32_16x16x32_bf16 v[150:153], v[214:217], v[226:229], v[150:153]
	ds_read_b128 v[214:217], v7 offset:37888
	v_mfma_f32_16x16x32_bf16 v[154:157], v[218:221], v[226:229], v[154:157]
	ds_read_b128 v[218:221], v7 offset:39936
	ds_read_b128 v[226:229], v6 offset:7168
	s_waitcnt lgkmcnt(6)
	v_mfma_f32_16x16x32_bf16 v[40:43], v[158:161], v[166:169], v[40:43]
	s_waitcnt lgkmcnt(5)
	s_mov_b32 m0, s62
	v_mfma_f32_16x16x32_bf16 v[44:47], v[162:165], v[166:169], v[44:47]
	global_load_lds_dwordx4 v146, s[64:65]
	s_waitcnt lgkmcnt(4)
	v_mfma_f32_16x16x32_bf16 v[56:59], v[158:161], v[178:181], v[56:59]
	v_mfma_f32_16x16x32_bf16 v[60:63], v[162:165], v[178:181], v[60:63]
	s_waitcnt lgkmcnt(3)
	v_mfma_f32_16x16x32_bf16 v[72:75], v[158:161], v[222:225], v[72:75]
	v_mfma_f32_16x16x32_bf16 v[76:79], v[162:165], v[222:225], v[76:79]
	s_waitcnt lgkmcnt(2)
	s_mov_b32 m0, s63
	v_mfma_f32_16x16x32_bf16 v[48:51], v[214:217], v[166:169], v[48:51]
	global_load_lds_dwordx4 v146, s[68:69]
	s_waitcnt lgkmcnt(1)
	v_mfma_f32_16x16x32_bf16 v[174:177], v[218:221], v[166:169], v[174:177]
	ds_read_b128 v[166:169], v6 offset:9216
	v_mfma_f32_16x16x32_bf16 v[64:67], v[214:217], v[178:181], v[64:67]
	v_mfma_f32_16x16x32_bf16 v[170:173], v[218:221], v[178:181], v[170:173]
	ds_read_b128 v[178:181], v6 offset:11264
	v_mfma_f32_16x16x32_bf16 v[80:83], v[214:217], v[222:225], v[80:83]
	v_mfma_f32_16x16x32_bf16 v[32:35], v[218:221], v[222:225], v[32:35]
	ds_read_b128 v[222:225], v6 offset:13312
	s_waitcnt lgkmcnt(3)
	v_mfma_f32_16x16x32_bf16 v[88:91], v[158:161], v[226:229], v[88:91]
	v_mfma_f32_16x16x32_bf16 v[92:95], v[162:165], v[226:229], v[92:95]
	v_mfma_f32_16x16x32_bf16 v[96:99], v[214:217], v[226:229], v[96:99]
	v_mfma_f32_16x16x32_bf16 v[36:39], v[218:221], v[226:229], v[36:39]
	ds_read_b128 v[226:229], v6 offset:15360
	s_waitcnt lgkmcnt(3)
	v_mfma_f32_16x16x32_bf16 v[104:107], v[158:161], v[166:169], v[104:107]
	v_mfma_f32_16x16x32_bf16 v[108:111], v[162:165], v[166:169], v[108:111]
	v_mfma_f32_16x16x32_bf16 v[112:115], v[214:217], v[166:169], v[112:115]
	v_mfma_f32_16x16x32_bf16 v[52:55], v[218:221], v[166:169], v[52:55]
	s_waitcnt lgkmcnt(2)
	v_mfma_f32_16x16x32_bf16 v[116:119], v[158:161], v[178:181], v[116:119]
	v_mfma_f32_16x16x32_bf16 v[120:123], v[162:165], v[178:181], v[120:123]
	v_mfma_f32_16x16x32_bf16 v[124:127], v[214:217], v[178:181], v[124:127]
	v_mfma_f32_16x16x32_bf16 v[68:71], v[218:221], v[178:181], v[68:71]
	s_waitcnt lgkmcnt(1)
	v_mfma_f32_16x16x32_bf16 v[128:131], v[158:161], v[222:225], v[128:131]
	v_mfma_f32_16x16x32_bf16 v[132:135], v[162:165], v[222:225], v[132:135]
	v_mfma_f32_16x16x32_bf16 v[136:139], v[214:217], v[222:225], v[136:139]
	v_mfma_f32_16x16x32_bf16 v[84:87], v[218:221], v[222:225], v[84:87]
	s_waitcnt lgkmcnt(0)
	v_mfma_f32_16x16x32_bf16 v[100:103], v[158:161], v[226:229], v[100:103]
	v_mfma_f32_16x16x32_bf16 v[140:143], v[162:165], v[226:229], v[140:143]
	v_mfma_f32_16x16x32_bf16 v[150:153], v[214:217], v[226:229], v[150:153]
	v_mfma_f32_16x16x32_bf16 v[154:157], v[218:221], v[226:229], v[154:157]
	s_add_u32 s64, s0, 0x1500
	s_addc_u32 s65, s1, 0
	s_add_u32 s68, s14, 0x1500
	s_waitcnt vmcnt(0)
	s_barrier
	s_addc_u32 s69, s15, 0
	ds_read_b128 v[158:161], v8
	ds_read_b128 v[162:165], v12
	ds_read_b128 v[166:169], v9
	ds_read_b128 v[178:181], v13
	ds_read_b128 v[214:217], v11
	ds_read_b128 v[218:221], v10
	ds_read_b128 v[222:225], v14
	ds_read_b128 v[226:229], v15
	s_waitcnt lgkmcnt(6)
	v_mfma_f32_16x16x32_bf16 v[40:43], v[158:161], v[162:165], v[40:43]
	s_waitcnt lgkmcnt(5)
	v_mfma_f32_16x16x32_bf16 v[44:47], v[166:169], v[162:165], v[44:47]
	s_waitcnt lgkmcnt(4)
	v_mfma_f32_16x16x32_bf16 v[56:59], v[158:161], v[178:181], v[56:59]
	s_mov_b32 m0, s42
	v_mfma_f32_16x16x32_bf16 v[60:63], v[166:169], v[178:181], v[60:63]
	global_load_lds_dwordx4 v0, s[64:65]
	s_waitcnt lgkmcnt(3)
	v_mfma_f32_16x16x32_bf16 v[48:51], v[214:217], v[162:165], v[48:51]
	v_mfma_f32_16x16x32_bf16 v[64:67], v[214:217], v[178:181], v[64:67]
	s_waitcnt lgkmcnt(2)
	v_mfma_f32_16x16x32_bf16 v[174:177], v[218:221], v[162:165], v[174:177]
	ds_read_b128 v[162:165], v16
	v_mfma_f32_16x16x32_bf16 v[170:173], v[218:221], v[178:181], v[170:173]
	ds_read_b128 v[178:181], v17
	s_waitcnt lgkmcnt(3)
	s_mov_b32 m0, s43
	v_mfma_f32_16x16x32_bf16 v[72:75], v[158:161], v[222:225], v[72:75]
	global_load_lds_dwordx4 v0, s[68:69]
	v_mfma_f32_16x16x32_bf16 v[76:79], v[166:169], v[222:225], v[76:79]
	v_mfma_f32_16x16x32_bf16 v[80:83], v[214:217], v[222:225], v[80:83]
	v_mfma_f32_16x16x32_bf16 v[32:35], v[218:221], v[222:225], v[32:35]
	ds_read_b128 v[222:225], v18
	s_waitcnt lgkmcnt(3)
	v_mfma_f32_16x16x32_bf16 v[88:91], v[158:161], v[226:229], v[88:91]
	s_mov_b32 m0, s44
	v_mfma_f32_16x16x32_bf16 v[92:95], v[166:169], v[226:229], v[92:95]
	global_load_lds_dwordx4 v2, s[64:65]
	v_mfma_f32_16x16x32_bf16 v[96:99], v[214:217], v[226:229], v[96:99]
	v_mfma_f32_16x16x32_bf16 v[36:39], v[218:221], v[226:229], v[36:39]
	ds_read_b128 v[226:229], v19
	s_waitcnt lgkmcnt(3)
	v_mfma_f32_16x16x32_bf16 v[104:107], v[158:161], v[162:165], v[104:107]
	s_waitcnt lgkmcnt(2)
	v_mfma_f32_16x16x32_bf16 v[116:119], v[158:161], v[178:181], v[116:119]
	s_waitcnt lgkmcnt(1)
	s_mov_b32 m0, s45
	v_mfma_f32_16x16x32_bf16 v[128:131], v[158:161], v[222:225], v[128:131]
	global_load_lds_dwordx4 v2, s[68:69]
	s_waitcnt lgkmcnt(0)
	v_mfma_f32_16x16x32_bf16 v[100:103], v[158:161], v[226:229], v[100:103]
	ds_read_b128 v[158:161], v20
	v_mfma_f32_16x16x32_bf16 v[108:111], v[166:169], v[162:165], v[108:111]
	v_mfma_f32_16x16x32_bf16 v[120:123], v[166:169], v[178:181], v[120:123]
	v_mfma_f32_16x16x32_bf16 v[132:135], v[166:169], v[222:225], v[132:135]
	s_mov_b32 m0, s46
	v_mfma_f32_16x16x32_bf16 v[140:143], v[166:169], v[226:229], v[140:143]
	global_load_lds_dwordx4 v4, s[64:65]
	ds_read_b128 v[166:169], v24
	v_mfma_f32_16x16x32_bf16 v[112:115], v[214:217], v[162:165], v[112:115]
	v_mfma_f32_16x16x32_bf16 v[52:55], v[218:221], v[162:165], v[52:55]
	ds_read_b128 v[162:165], v21
	v_mfma_f32_16x16x32_bf16 v[124:127], v[214:217], v[178:181], v[124:127]
	v_mfma_f32_16x16x32_bf16 v[68:71], v[218:221], v[178:181], v[68:71]
	ds_read_b128 v[178:181], v25
	s_mov_b32 m0, s47
	v_mfma_f32_16x16x32_bf16 v[136:139], v[214:217], v[222:225], v[136:139]
	global_load_lds_dwordx4 v4, s[68:69]
	v_mfma_f32_16x16x32_bf16 v[84:87], v[218:221], v[222:225], v[84:87]
	ds_read_b128 v[222:225], v26
	v_mfma_f32_16x16x32_bf16 v[150:153], v[214:217], v[226:229], v[150:153]
	ds_read_b128 v[214:217], v23
	v_mfma_f32_16x16x32_bf16 v[154:157], v[218:221], v[226:229], v[154:157]
	ds_read_b128 v[218:221], v22
	ds_read_b128 v[226:229], v27
	s_waitcnt lgkmcnt(6)
	v_mfma_f32_16x16x32_bf16 v[40:43], v[158:161], v[166:169], v[40:43]
	s_waitcnt lgkmcnt(5)
	s_mov_b32 m0, s49
	v_mfma_f32_16x16x32_bf16 v[44:47], v[162:165], v[166:169], v[44:47]
	global_load_lds_dwordx4 v146, s[64:65]
	s_waitcnt lgkmcnt(4)
	v_mfma_f32_16x16x32_bf16 v[56:59], v[158:161], v[178:181], v[56:59]
	v_mfma_f32_16x16x32_bf16 v[60:63], v[162:165], v[178:181], v[60:63]
	s_waitcnt lgkmcnt(3)
	v_mfma_f32_16x16x32_bf16 v[72:75], v[158:161], v[222:225], v[72:75]
	v_mfma_f32_16x16x32_bf16 v[76:79], v[162:165], v[222:225], v[76:79]
	s_waitcnt lgkmcnt(2)
	s_mov_b32 m0, s50
	v_mfma_f32_16x16x32_bf16 v[48:51], v[214:217], v[166:169], v[48:51]
	global_load_lds_dwordx4 v146, s[68:69]
	s_waitcnt lgkmcnt(1)
	v_mfma_f32_16x16x32_bf16 v[174:177], v[218:221], v[166:169], v[174:177]
	ds_read_b128 v[166:169], v28
	v_mfma_f32_16x16x32_bf16 v[64:67], v[214:217], v[178:181], v[64:67]
	v_mfma_f32_16x16x32_bf16 v[170:173], v[218:221], v[178:181], v[170:173]
	ds_read_b128 v[178:181], v29
	v_mfma_f32_16x16x32_bf16 v[80:83], v[214:217], v[222:225], v[80:83]
	v_mfma_f32_16x16x32_bf16 v[32:35], v[218:221], v[222:225], v[32:35]
	ds_read_b128 v[222:225], v30
	s_waitcnt lgkmcnt(3)
	v_mfma_f32_16x16x32_bf16 v[88:91], v[158:161], v[226:229], v[88:91]
	v_mfma_f32_16x16x32_bf16 v[92:95], v[162:165], v[226:229], v[92:95]
	v_mfma_f32_16x16x32_bf16 v[96:99], v[214:217], v[226:229], v[96:99]
	v_mfma_f32_16x16x32_bf16 v[36:39], v[218:221], v[226:229], v[36:39]
	ds_read_b128 v[226:229], v31
	s_waitcnt lgkmcnt(3)
	v_mfma_f32_16x16x32_bf16 v[104:107], v[158:161], v[166:169], v[104:107]
	v_mfma_f32_16x16x32_bf16 v[108:111], v[162:165], v[166:169], v[108:111]
	v_mfma_f32_16x16x32_bf16 v[112:115], v[214:217], v[166:169], v[112:115]
	v_mfma_f32_16x16x32_bf16 v[52:55], v[218:221], v[166:169], v[52:55]
	s_waitcnt lgkmcnt(2)
	v_mfma_f32_16x16x32_bf16 v[116:119], v[158:161], v[178:181], v[116:119]
	v_mfma_f32_16x16x32_bf16 v[120:123], v[162:165], v[178:181], v[120:123]
	v_mfma_f32_16x16x32_bf16 v[124:127], v[214:217], v[178:181], v[124:127]
	v_mfma_f32_16x16x32_bf16 v[68:71], v[218:221], v[178:181], v[68:71]
	s_waitcnt lgkmcnt(1)
	v_mfma_f32_16x16x32_bf16 v[128:131], v[158:161], v[222:225], v[128:131]
	v_mfma_f32_16x16x32_bf16 v[132:135], v[162:165], v[222:225], v[132:135]
	v_mfma_f32_16x16x32_bf16 v[136:139], v[214:217], v[222:225], v[136:139]
	v_mfma_f32_16x16x32_bf16 v[84:87], v[218:221], v[222:225], v[84:87]
	s_waitcnt lgkmcnt(0)
	v_mfma_f32_16x16x32_bf16 v[100:103], v[158:161], v[226:229], v[100:103]
	v_mfma_f32_16x16x32_bf16 v[140:143], v[162:165], v[226:229], v[140:143]
	v_mfma_f32_16x16x32_bf16 v[150:153], v[214:217], v[226:229], v[150:153]
	v_mfma_f32_16x16x32_bf16 v[154:157], v[218:221], v[226:229], v[154:157]
	s_add_u32 s64, s0, 0x1580
	s_addc_u32 s65, s1, 0
	s_add_u32 s68, s14, 0x1580
	s_waitcnt vmcnt(0)
	s_barrier
	s_addc_u32 s69, s15, 0
	ds_read_b128 v[158:161], v7 offset:32768
	ds_read_b128 v[162:165], v6
	ds_read_b128 v[166:169], v7 offset:34816
	ds_read_b128 v[178:181], v6 offset:2048
	ds_read_b128 v[214:217], v7 offset:36864
	ds_read_b128 v[218:221], v7 offset:38912
	ds_read_b128 v[222:225], v6 offset:4096
	ds_read_b128 v[226:229], v6 offset:6144
	s_waitcnt lgkmcnt(6)
	v_mfma_f32_16x16x32_bf16 v[40:43], v[158:161], v[162:165], v[40:43]
	s_waitcnt lgkmcnt(5)
	v_mfma_f32_16x16x32_bf16 v[44:47], v[166:169], v[162:165], v[44:47]
	s_waitcnt lgkmcnt(4)
	v_mfma_f32_16x16x32_bf16 v[56:59], v[158:161], v[178:181], v[56:59]
	s_mov_b32 m0, s52
	v_mfma_f32_16x16x32_bf16 v[60:63], v[166:169], v[178:181], v[60:63]
	global_load_lds_dwordx4 v0, s[64:65]
	s_waitcnt lgkmcnt(3)
	v_mfma_f32_16x16x32_bf16 v[48:51], v[214:217], v[162:165], v[48:51]
	v_mfma_f32_16x16x32_bf16 v[64:67], v[214:217], v[178:181], v[64:67]
	s_waitcnt lgkmcnt(2)
	v_mfma_f32_16x16x32_bf16 v[174:177], v[218:221], v[162:165], v[174:177]
	ds_read_b128 v[162:165], v6 offset:8192
	v_mfma_f32_16x16x32_bf16 v[170:173], v[218:221], v[178:181], v[170:173]
	ds_read_b128 v[178:181], v6 offset:10240
	s_waitcnt lgkmcnt(3)
	s_mov_b32 m0, s51
	v_mfma_f32_16x16x32_bf16 v[72:75], v[158:161], v[222:225], v[72:75]
	global_load_lds_dwordx4 v0, s[68:69]
	v_mfma_f32_16x16x32_bf16 v[76:79], v[166:169], v[222:225], v[76:79]
	v_mfma_f32_16x16x32_bf16 v[80:83], v[214:217], v[222:225], v[80:83]
	v_mfma_f32_16x16x32_bf16 v[32:35], v[218:221], v[222:225], v[32:35]
	ds_read_b128 v[222:225], v6 offset:12288
	s_waitcnt lgkmcnt(3)
	v_mfma_f32_16x16x32_bf16 v[88:91], v[158:161], v[226:229], v[88:91]
	s_mov_b32 m0, s53
	v_mfma_f32_16x16x32_bf16 v[92:95], v[166:169], v[226:229], v[92:95]
	global_load_lds_dwordx4 v2, s[64:65]
	v_mfma_f32_16x16x32_bf16 v[96:99], v[214:217], v[226:229], v[96:99]
	v_mfma_f32_16x16x32_bf16 v[36:39], v[218:221], v[226:229], v[36:39]
	ds_read_b128 v[226:229], v6 offset:14336
	s_waitcnt lgkmcnt(3)
	v_mfma_f32_16x16x32_bf16 v[104:107], v[158:161], v[162:165], v[104:107]
	s_waitcnt lgkmcnt(2)
	v_mfma_f32_16x16x32_bf16 v[116:119], v[158:161], v[178:181], v[116:119]
	s_waitcnt lgkmcnt(1)
	s_mov_b32 m0, s54
	v_mfma_f32_16x16x32_bf16 v[128:131], v[158:161], v[222:225], v[128:131]
	global_load_lds_dwordx4 v2, s[68:69]
	s_waitcnt lgkmcnt(0)
	v_mfma_f32_16x16x32_bf16 v[100:103], v[158:161], v[226:229], v[100:103]
	ds_read_b128 v[158:161], v7 offset:33792
	v_mfma_f32_16x16x32_bf16 v[108:111], v[166:169], v[162:165], v[108:111]
	v_mfma_f32_16x16x32_bf16 v[120:123], v[166:169], v[178:181], v[120:123]
	v_mfma_f32_16x16x32_bf16 v[132:135], v[166:169], v[222:225], v[132:135]
	s_mov_b32 m0, s55
	v_mfma_f32_16x16x32_bf16 v[140:143], v[166:169], v[226:229], v[140:143]
	global_load_lds_dwordx4 v4, s[64:65]
	ds_read_b128 v[166:169], v6 offset:1024
	v_mfma_f32_16x16x32_bf16 v[112:115], v[214:217], v[162:165], v[112:115]
	v_mfma_f32_16x16x32_bf16 v[52:55], v[218:221], v[162:165], v[52:55]
	ds_read_b128 v[162:165], v7 offset:35840
	v_mfma_f32_16x16x32_bf16 v[124:127], v[214:217], v[178:181], v[124:127]
	v_mfma_f32_16x16x32_bf16 v[68:71], v[218:221], v[178:181], v[68:71]
	ds_read_b128 v[178:181], v6 offset:3072
	s_mov_b32 m0, s58
	v_mfma_f32_16x16x32_bf16 v[136:139], v[214:217], v[222:225], v[136:139]
	global_load_lds_dwordx4 v4, s[68:69]
	v_mfma_f32_16x16x32_bf16 v[84:87], v[218:221], v[222:225], v[84:87]
	ds_read_b128 v[222:225], v6 offset:5120
	v_mfma_f32_16x16x32_bf16 v[150:153], v[214:217], v[226:229], v[150:153]
	ds_read_b128 v[214:217], v7 offset:37888
	v_mfma_f32_16x16x32_bf16 v[154:157], v[218:221], v[226:229], v[154:157]
	ds_read_b128 v[218:221], v7 offset:39936
	ds_read_b128 v[226:229], v6 offset:7168
	s_waitcnt lgkmcnt(6)
	v_mfma_f32_16x16x32_bf16 v[40:43], v[158:161], v[166:169], v[40:43]
	s_waitcnt lgkmcnt(5)
	s_mov_b32 m0, s62
	v_mfma_f32_16x16x32_bf16 v[44:47], v[162:165], v[166:169], v[44:47]
	global_load_lds_dwordx4 v146, s[64:65]
	s_waitcnt lgkmcnt(4)
	v_mfma_f32_16x16x32_bf16 v[56:59], v[158:161], v[178:181], v[56:59]
	v_mfma_f32_16x16x32_bf16 v[60:63], v[162:165], v[178:181], v[60:63]
	s_waitcnt lgkmcnt(3)
	v_mfma_f32_16x16x32_bf16 v[72:75], v[158:161], v[222:225], v[72:75]
	v_mfma_f32_16x16x32_bf16 v[76:79], v[162:165], v[222:225], v[76:79]
	s_waitcnt lgkmcnt(2)
	s_mov_b32 m0, s63
	v_mfma_f32_16x16x32_bf16 v[48:51], v[214:217], v[166:169], v[48:51]
	global_load_lds_dwordx4 v146, s[68:69]
	s_waitcnt lgkmcnt(1)
	v_mfma_f32_16x16x32_bf16 v[174:177], v[218:221], v[166:169], v[174:177]
	ds_read_b128 v[166:169], v6 offset:9216
	v_mfma_f32_16x16x32_bf16 v[64:67], v[214:217], v[178:181], v[64:67]
	v_mfma_f32_16x16x32_bf16 v[170:173], v[218:221], v[178:181], v[170:173]
	ds_read_b128 v[178:181], v6 offset:11264
	v_mfma_f32_16x16x32_bf16 v[80:83], v[214:217], v[222:225], v[80:83]
	v_mfma_f32_16x16x32_bf16 v[32:35], v[218:221], v[222:225], v[32:35]
	ds_read_b128 v[222:225], v6 offset:13312
	s_waitcnt lgkmcnt(3)
	v_mfma_f32_16x16x32_bf16 v[88:91], v[158:161], v[226:229], v[88:91]
	v_mfma_f32_16x16x32_bf16 v[92:95], v[162:165], v[226:229], v[92:95]
	v_mfma_f32_16x16x32_bf16 v[96:99], v[214:217], v[226:229], v[96:99]
	v_mfma_f32_16x16x32_bf16 v[36:39], v[218:221], v[226:229], v[36:39]
	ds_read_b128 v[226:229], v6 offset:15360
	s_waitcnt lgkmcnt(3)
	v_mfma_f32_16x16x32_bf16 v[104:107], v[158:161], v[166:169], v[104:107]
	v_mfma_f32_16x16x32_bf16 v[108:111], v[162:165], v[166:169], v[108:111]
	v_mfma_f32_16x16x32_bf16 v[112:115], v[214:217], v[166:169], v[112:115]
	v_mfma_f32_16x16x32_bf16 v[52:55], v[218:221], v[166:169], v[52:55]
	s_waitcnt lgkmcnt(2)
	v_mfma_f32_16x16x32_bf16 v[116:119], v[158:161], v[178:181], v[116:119]
	v_mfma_f32_16x16x32_bf16 v[120:123], v[162:165], v[178:181], v[120:123]
	v_mfma_f32_16x16x32_bf16 v[124:127], v[214:217], v[178:181], v[124:127]
	v_mfma_f32_16x16x32_bf16 v[68:71], v[218:221], v[178:181], v[68:71]
	s_waitcnt lgkmcnt(1)
	v_mfma_f32_16x16x32_bf16 v[128:131], v[158:161], v[222:225], v[128:131]
	v_mfma_f32_16x16x32_bf16 v[132:135], v[162:165], v[222:225], v[132:135]
	v_mfma_f32_16x16x32_bf16 v[136:139], v[214:217], v[222:225], v[136:139]
	v_mfma_f32_16x16x32_bf16 v[84:87], v[218:221], v[222:225], v[84:87]
	s_waitcnt lgkmcnt(0)
	v_mfma_f32_16x16x32_bf16 v[100:103], v[158:161], v[226:229], v[100:103]
	v_mfma_f32_16x16x32_bf16 v[140:143], v[162:165], v[226:229], v[140:143]
	v_mfma_f32_16x16x32_bf16 v[150:153], v[214:217], v[226:229], v[150:153]
	v_mfma_f32_16x16x32_bf16 v[154:157], v[218:221], v[226:229], v[154:157]
	s_add_u32 s64, s0, 0x1600
	s_addc_u32 s65, s1, 0
	s_add_u32 s68, s14, 0x1600
	s_waitcnt vmcnt(0)
	s_barrier
	s_addc_u32 s69, s15, 0
	ds_read_b128 v[158:161], v8
	ds_read_b128 v[162:165], v12
	ds_read_b128 v[166:169], v9
	ds_read_b128 v[178:181], v13
	ds_read_b128 v[214:217], v11
	ds_read_b128 v[218:221], v10
	ds_read_b128 v[222:225], v14
	ds_read_b128 v[226:229], v15
	s_waitcnt lgkmcnt(6)
	v_mfma_f32_16x16x32_bf16 v[40:43], v[158:161], v[162:165], v[40:43]
	s_waitcnt lgkmcnt(5)
	v_mfma_f32_16x16x32_bf16 v[44:47], v[166:169], v[162:165], v[44:47]
	s_waitcnt lgkmcnt(4)
	v_mfma_f32_16x16x32_bf16 v[56:59], v[158:161], v[178:181], v[56:59]
	s_mov_b32 m0, s42
	v_mfma_f32_16x16x32_bf16 v[60:63], v[166:169], v[178:181], v[60:63]
	global_load_lds_dwordx4 v0, s[64:65]
	s_waitcnt lgkmcnt(3)
	v_mfma_f32_16x16x32_bf16 v[48:51], v[214:217], v[162:165], v[48:51]
	v_mfma_f32_16x16x32_bf16 v[64:67], v[214:217], v[178:181], v[64:67]
	s_waitcnt lgkmcnt(2)
	v_mfma_f32_16x16x32_bf16 v[174:177], v[218:221], v[162:165], v[174:177]
	ds_read_b128 v[162:165], v16
	v_mfma_f32_16x16x32_bf16 v[170:173], v[218:221], v[178:181], v[170:173]
	ds_read_b128 v[178:181], v17
	s_waitcnt lgkmcnt(3)
	s_mov_b32 m0, s43
	v_mfma_f32_16x16x32_bf16 v[72:75], v[158:161], v[222:225], v[72:75]
	global_load_lds_dwordx4 v0, s[68:69]
	v_mfma_f32_16x16x32_bf16 v[76:79], v[166:169], v[222:225], v[76:79]
	v_mfma_f32_16x16x32_bf16 v[80:83], v[214:217], v[222:225], v[80:83]
	v_mfma_f32_16x16x32_bf16 v[32:35], v[218:221], v[222:225], v[32:35]
	ds_read_b128 v[222:225], v18
	s_waitcnt lgkmcnt(3)
	v_mfma_f32_16x16x32_bf16 v[88:91], v[158:161], v[226:229], v[88:91]
	s_mov_b32 m0, s44
	v_mfma_f32_16x16x32_bf16 v[92:95], v[166:169], v[226:229], v[92:95]
	global_load_lds_dwordx4 v2, s[64:65]
	v_mfma_f32_16x16x32_bf16 v[96:99], v[214:217], v[226:229], v[96:99]
	v_mfma_f32_16x16x32_bf16 v[36:39], v[218:221], v[226:229], v[36:39]
	ds_read_b128 v[226:229], v19
	s_waitcnt lgkmcnt(3)
	v_mfma_f32_16x16x32_bf16 v[104:107], v[158:161], v[162:165], v[104:107]
	s_waitcnt lgkmcnt(2)
	v_mfma_f32_16x16x32_bf16 v[116:119], v[158:161], v[178:181], v[116:119]
	s_waitcnt lgkmcnt(1)
	s_mov_b32 m0, s45
	v_mfma_f32_16x16x32_bf16 v[128:131], v[158:161], v[222:225], v[128:131]
	global_load_lds_dwordx4 v2, s[68:69]
	s_waitcnt lgkmcnt(0)
	v_mfma_f32_16x16x32_bf16 v[100:103], v[158:161], v[226:229], v[100:103]
	ds_read_b128 v[158:161], v20
	v_mfma_f32_16x16x32_bf16 v[108:111], v[166:169], v[162:165], v[108:111]
	v_mfma_f32_16x16x32_bf16 v[120:123], v[166:169], v[178:181], v[120:123]
	v_mfma_f32_16x16x32_bf16 v[132:135], v[166:169], v[222:225], v[132:135]
	s_mov_b32 m0, s46
	v_mfma_f32_16x16x32_bf16 v[140:143], v[166:169], v[226:229], v[140:143]
	global_load_lds_dwordx4 v4, s[64:65]
	ds_read_b128 v[166:169], v24
	v_mfma_f32_16x16x32_bf16 v[112:115], v[214:217], v[162:165], v[112:115]
	v_mfma_f32_16x16x32_bf16 v[52:55], v[218:221], v[162:165], v[52:55]
	ds_read_b128 v[162:165], v21
	v_mfma_f32_16x16x32_bf16 v[124:127], v[214:217], v[178:181], v[124:127]
	v_mfma_f32_16x16x32_bf16 v[68:71], v[218:221], v[178:181], v[68:71]
	ds_read_b128 v[178:181], v25
	s_mov_b32 m0, s47
	v_mfma_f32_16x16x32_bf16 v[136:139], v[214:217], v[222:225], v[136:139]
	global_load_lds_dwordx4 v4, s[68:69]
	v_mfma_f32_16x16x32_bf16 v[84:87], v[218:221], v[222:225], v[84:87]
	ds_read_b128 v[222:225], v26
	v_mfma_f32_16x16x32_bf16 v[150:153], v[214:217], v[226:229], v[150:153]
	ds_read_b128 v[214:217], v23
	v_mfma_f32_16x16x32_bf16 v[154:157], v[218:221], v[226:229], v[154:157]
	ds_read_b128 v[218:221], v22
	ds_read_b128 v[226:229], v27
	s_waitcnt lgkmcnt(6)
	v_mfma_f32_16x16x32_bf16 v[40:43], v[158:161], v[166:169], v[40:43]
	s_waitcnt lgkmcnt(5)
	s_mov_b32 m0, s49
	v_mfma_f32_16x16x32_bf16 v[44:47], v[162:165], v[166:169], v[44:47]
	global_load_lds_dwordx4 v146, s[64:65]
	s_waitcnt lgkmcnt(4)
	v_mfma_f32_16x16x32_bf16 v[56:59], v[158:161], v[178:181], v[56:59]
	v_mfma_f32_16x16x32_bf16 v[60:63], v[162:165], v[178:181], v[60:63]
	s_waitcnt lgkmcnt(3)
	v_mfma_f32_16x16x32_bf16 v[72:75], v[158:161], v[222:225], v[72:75]
	v_mfma_f32_16x16x32_bf16 v[76:79], v[162:165], v[222:225], v[76:79]
	s_waitcnt lgkmcnt(2)
	s_mov_b32 m0, s50
	v_mfma_f32_16x16x32_bf16 v[48:51], v[214:217], v[166:169], v[48:51]
	global_load_lds_dwordx4 v146, s[68:69]
	s_waitcnt lgkmcnt(1)
	v_mfma_f32_16x16x32_bf16 v[174:177], v[218:221], v[166:169], v[174:177]
	ds_read_b128 v[166:169], v28
	v_mfma_f32_16x16x32_bf16 v[64:67], v[214:217], v[178:181], v[64:67]
	v_mfma_f32_16x16x32_bf16 v[170:173], v[218:221], v[178:181], v[170:173]
	ds_read_b128 v[178:181], v29
	v_mfma_f32_16x16x32_bf16 v[80:83], v[214:217], v[222:225], v[80:83]
	v_mfma_f32_16x16x32_bf16 v[32:35], v[218:221], v[222:225], v[32:35]
	ds_read_b128 v[222:225], v30
	s_waitcnt lgkmcnt(3)
	v_mfma_f32_16x16x32_bf16 v[88:91], v[158:161], v[226:229], v[88:91]
	v_mfma_f32_16x16x32_bf16 v[92:95], v[162:165], v[226:229], v[92:95]
	v_mfma_f32_16x16x32_bf16 v[96:99], v[214:217], v[226:229], v[96:99]
	v_mfma_f32_16x16x32_bf16 v[36:39], v[218:221], v[226:229], v[36:39]
	ds_read_b128 v[226:229], v31
	s_waitcnt lgkmcnt(3)
	v_mfma_f32_16x16x32_bf16 v[104:107], v[158:161], v[166:169], v[104:107]
	v_mfma_f32_16x16x32_bf16 v[108:111], v[162:165], v[166:169], v[108:111]
	v_mfma_f32_16x16x32_bf16 v[112:115], v[214:217], v[166:169], v[112:115]
	v_mfma_f32_16x16x32_bf16 v[52:55], v[218:221], v[166:169], v[52:55]
	s_waitcnt lgkmcnt(2)
	v_mfma_f32_16x16x32_bf16 v[116:119], v[158:161], v[178:181], v[116:119]
	v_mfma_f32_16x16x32_bf16 v[120:123], v[162:165], v[178:181], v[120:123]
	v_mfma_f32_16x16x32_bf16 v[124:127], v[214:217], v[178:181], v[124:127]
	v_mfma_f32_16x16x32_bf16 v[68:71], v[218:221], v[178:181], v[68:71]
	s_waitcnt lgkmcnt(1)
	v_mfma_f32_16x16x32_bf16 v[128:131], v[158:161], v[222:225], v[128:131]
	v_mfma_f32_16x16x32_bf16 v[132:135], v[162:165], v[222:225], v[132:135]
	v_mfma_f32_16x16x32_bf16 v[136:139], v[214:217], v[222:225], v[136:139]
	v_mfma_f32_16x16x32_bf16 v[84:87], v[218:221], v[222:225], v[84:87]
	s_waitcnt lgkmcnt(0)
	v_mfma_f32_16x16x32_bf16 v[100:103], v[158:161], v[226:229], v[100:103]
	v_mfma_f32_16x16x32_bf16 v[140:143], v[162:165], v[226:229], v[140:143]
	v_mfma_f32_16x16x32_bf16 v[150:153], v[214:217], v[226:229], v[150:153]
	v_mfma_f32_16x16x32_bf16 v[154:157], v[218:221], v[226:229], v[154:157]
	s_add_u32 s64, s0, 0x1680
	s_addc_u32 s65, s1, 0
	s_add_u32 s68, s14, 0x1680
	s_waitcnt vmcnt(0)
	s_barrier
	s_addc_u32 s69, s15, 0
	ds_read_b128 v[158:161], v7 offset:32768
	ds_read_b128 v[162:165], v6
	ds_read_b128 v[166:169], v7 offset:34816
	ds_read_b128 v[178:181], v6 offset:2048
	ds_read_b128 v[214:217], v7 offset:36864
	ds_read_b128 v[218:221], v7 offset:38912
	ds_read_b128 v[222:225], v6 offset:4096
	ds_read_b128 v[226:229], v6 offset:6144
	s_waitcnt lgkmcnt(6)
	v_mfma_f32_16x16x32_bf16 v[40:43], v[158:161], v[162:165], v[40:43]
	s_waitcnt lgkmcnt(5)
	v_mfma_f32_16x16x32_bf16 v[44:47], v[166:169], v[162:165], v[44:47]
	s_waitcnt lgkmcnt(4)
	v_mfma_f32_16x16x32_bf16 v[56:59], v[158:161], v[178:181], v[56:59]
	s_mov_b32 m0, s52
	v_mfma_f32_16x16x32_bf16 v[60:63], v[166:169], v[178:181], v[60:63]
	global_load_lds_dwordx4 v0, s[64:65]
	s_waitcnt lgkmcnt(3)
	v_mfma_f32_16x16x32_bf16 v[48:51], v[214:217], v[162:165], v[48:51]
	v_mfma_f32_16x16x32_bf16 v[64:67], v[214:217], v[178:181], v[64:67]
	s_waitcnt lgkmcnt(2)
	v_mfma_f32_16x16x32_bf16 v[174:177], v[218:221], v[162:165], v[174:177]
	ds_read_b128 v[162:165], v6 offset:8192
	v_mfma_f32_16x16x32_bf16 v[170:173], v[218:221], v[178:181], v[170:173]
	ds_read_b128 v[178:181], v6 offset:10240
	s_waitcnt lgkmcnt(3)
	s_mov_b32 m0, s51
	v_mfma_f32_16x16x32_bf16 v[72:75], v[158:161], v[222:225], v[72:75]
	global_load_lds_dwordx4 v0, s[68:69]
	v_mfma_f32_16x16x32_bf16 v[76:79], v[166:169], v[222:225], v[76:79]
	v_mfma_f32_16x16x32_bf16 v[80:83], v[214:217], v[222:225], v[80:83]
	v_mfma_f32_16x16x32_bf16 v[32:35], v[218:221], v[222:225], v[32:35]
	ds_read_b128 v[222:225], v6 offset:12288
	s_waitcnt lgkmcnt(3)
	v_mfma_f32_16x16x32_bf16 v[88:91], v[158:161], v[226:229], v[88:91]
	s_mov_b32 m0, s53
	v_mfma_f32_16x16x32_bf16 v[92:95], v[166:169], v[226:229], v[92:95]
	global_load_lds_dwordx4 v2, s[64:65]
	v_mfma_f32_16x16x32_bf16 v[96:99], v[214:217], v[226:229], v[96:99]
	v_mfma_f32_16x16x32_bf16 v[36:39], v[218:221], v[226:229], v[36:39]
	ds_read_b128 v[226:229], v6 offset:14336
	s_waitcnt lgkmcnt(3)
	v_mfma_f32_16x16x32_bf16 v[104:107], v[158:161], v[162:165], v[104:107]
	s_waitcnt lgkmcnt(2)
	v_mfma_f32_16x16x32_bf16 v[116:119], v[158:161], v[178:181], v[116:119]
	s_waitcnt lgkmcnt(1)
	s_mov_b32 m0, s54
	v_mfma_f32_16x16x32_bf16 v[128:131], v[158:161], v[222:225], v[128:131]
	global_load_lds_dwordx4 v2, s[68:69]
	s_waitcnt lgkmcnt(0)
	v_mfma_f32_16x16x32_bf16 v[100:103], v[158:161], v[226:229], v[100:103]
	ds_read_b128 v[158:161], v7 offset:33792
	v_mfma_f32_16x16x32_bf16 v[108:111], v[166:169], v[162:165], v[108:111]
	v_mfma_f32_16x16x32_bf16 v[120:123], v[166:169], v[178:181], v[120:123]
	v_mfma_f32_16x16x32_bf16 v[132:135], v[166:169], v[222:225], v[132:135]
	s_mov_b32 m0, s55
	v_mfma_f32_16x16x32_bf16 v[140:143], v[166:169], v[226:229], v[140:143]
	global_load_lds_dwordx4 v4, s[64:65]
	ds_read_b128 v[166:169], v6 offset:1024
	v_mfma_f32_16x16x32_bf16 v[112:115], v[214:217], v[162:165], v[112:115]
	v_mfma_f32_16x16x32_bf16 v[52:55], v[218:221], v[162:165], v[52:55]
	ds_read_b128 v[162:165], v7 offset:35840
	v_mfma_f32_16x16x32_bf16 v[124:127], v[214:217], v[178:181], v[124:127]
	v_mfma_f32_16x16x32_bf16 v[68:71], v[218:221], v[178:181], v[68:71]
	ds_read_b128 v[178:181], v6 offset:3072
	s_mov_b32 m0, s58
	v_mfma_f32_16x16x32_bf16 v[136:139], v[214:217], v[222:225], v[136:139]
	global_load_lds_dwordx4 v4, s[68:69]
	v_mfma_f32_16x16x32_bf16 v[84:87], v[218:221], v[222:225], v[84:87]
	ds_read_b128 v[222:225], v6 offset:5120
	v_mfma_f32_16x16x32_bf16 v[150:153], v[214:217], v[226:229], v[150:153]
	ds_read_b128 v[214:217], v7 offset:37888
	v_mfma_f32_16x16x32_bf16 v[154:157], v[218:221], v[226:229], v[154:157]
	ds_read_b128 v[218:221], v7 offset:39936
	ds_read_b128 v[226:229], v6 offset:7168
	s_waitcnt lgkmcnt(6)
	v_mfma_f32_16x16x32_bf16 v[40:43], v[158:161], v[166:169], v[40:43]
	s_waitcnt lgkmcnt(5)
	s_mov_b32 m0, s62
	v_mfma_f32_16x16x32_bf16 v[44:47], v[162:165], v[166:169], v[44:47]
	global_load_lds_dwordx4 v146, s[64:65]
	s_waitcnt lgkmcnt(4)
	v_mfma_f32_16x16x32_bf16 v[56:59], v[158:161], v[178:181], v[56:59]
	v_mfma_f32_16x16x32_bf16 v[60:63], v[162:165], v[178:181], v[60:63]
	s_waitcnt lgkmcnt(3)
	v_mfma_f32_16x16x32_bf16 v[72:75], v[158:161], v[222:225], v[72:75]
	v_mfma_f32_16x16x32_bf16 v[76:79], v[162:165], v[222:225], v[76:79]
	s_waitcnt lgkmcnt(2)
	s_mov_b32 m0, s63
	v_mfma_f32_16x16x32_bf16 v[48:51], v[214:217], v[166:169], v[48:51]
	global_load_lds_dwordx4 v146, s[68:69]
	s_waitcnt lgkmcnt(1)
	v_mfma_f32_16x16x32_bf16 v[174:177], v[218:221], v[166:169], v[174:177]
	ds_read_b128 v[166:169], v6 offset:9216
	v_mfma_f32_16x16x32_bf16 v[64:67], v[214:217], v[178:181], v[64:67]
	v_mfma_f32_16x16x32_bf16 v[170:173], v[218:221], v[178:181], v[170:173]
	ds_read_b128 v[178:181], v6 offset:11264
	v_mfma_f32_16x16x32_bf16 v[80:83], v[214:217], v[222:225], v[80:83]
	v_mfma_f32_16x16x32_bf16 v[32:35], v[218:221], v[222:225], v[32:35]
	ds_read_b128 v[222:225], v6 offset:13312
	s_waitcnt lgkmcnt(3)
	v_mfma_f32_16x16x32_bf16 v[88:91], v[158:161], v[226:229], v[88:91]
	v_mfma_f32_16x16x32_bf16 v[92:95], v[162:165], v[226:229], v[92:95]
	v_mfma_f32_16x16x32_bf16 v[96:99], v[214:217], v[226:229], v[96:99]
	v_mfma_f32_16x16x32_bf16 v[36:39], v[218:221], v[226:229], v[36:39]
	ds_read_b128 v[226:229], v6 offset:15360
	s_waitcnt lgkmcnt(3)
	v_mfma_f32_16x16x32_bf16 v[104:107], v[158:161], v[166:169], v[104:107]
	v_mfma_f32_16x16x32_bf16 v[108:111], v[162:165], v[166:169], v[108:111]
	v_mfma_f32_16x16x32_bf16 v[112:115], v[214:217], v[166:169], v[112:115]
	v_mfma_f32_16x16x32_bf16 v[52:55], v[218:221], v[166:169], v[52:55]
	s_waitcnt lgkmcnt(2)
	v_mfma_f32_16x16x32_bf16 v[116:119], v[158:161], v[178:181], v[116:119]
	v_mfma_f32_16x16x32_bf16 v[120:123], v[162:165], v[178:181], v[120:123]
	v_mfma_f32_16x16x32_bf16 v[124:127], v[214:217], v[178:181], v[124:127]
	v_mfma_f32_16x16x32_bf16 v[68:71], v[218:221], v[178:181], v[68:71]
	s_waitcnt lgkmcnt(1)
	v_mfma_f32_16x16x32_bf16 v[128:131], v[158:161], v[222:225], v[128:131]
	v_mfma_f32_16x16x32_bf16 v[132:135], v[162:165], v[222:225], v[132:135]
	v_mfma_f32_16x16x32_bf16 v[136:139], v[214:217], v[222:225], v[136:139]
	v_mfma_f32_16x16x32_bf16 v[84:87], v[218:221], v[222:225], v[84:87]
	s_waitcnt lgkmcnt(0)
	v_mfma_f32_16x16x32_bf16 v[100:103], v[158:161], v[226:229], v[100:103]
	v_mfma_f32_16x16x32_bf16 v[140:143], v[162:165], v[226:229], v[140:143]
	v_mfma_f32_16x16x32_bf16 v[150:153], v[214:217], v[226:229], v[150:153]
	v_mfma_f32_16x16x32_bf16 v[154:157], v[218:221], v[226:229], v[154:157]
	s_add_u32 s64, s0, 0x1700
	s_addc_u32 s65, s1, 0
	s_add_u32 s68, s14, 0x1700
	s_waitcnt vmcnt(0)
	s_barrier
	s_addc_u32 s69, s15, 0
	ds_read_b128 v[158:161], v8
	ds_read_b128 v[162:165], v12
	ds_read_b128 v[166:169], v9
	ds_read_b128 v[178:181], v13
	ds_read_b128 v[214:217], v11
	ds_read_b128 v[218:221], v10
	ds_read_b128 v[222:225], v14
	ds_read_b128 v[226:229], v15
	s_waitcnt lgkmcnt(6)
	v_mfma_f32_16x16x32_bf16 v[40:43], v[158:161], v[162:165], v[40:43]
	s_waitcnt lgkmcnt(5)
	v_mfma_f32_16x16x32_bf16 v[44:47], v[166:169], v[162:165], v[44:47]
	s_waitcnt lgkmcnt(4)
	v_mfma_f32_16x16x32_bf16 v[56:59], v[158:161], v[178:181], v[56:59]
	s_mov_b32 m0, s42
	v_mfma_f32_16x16x32_bf16 v[60:63], v[166:169], v[178:181], v[60:63]
	global_load_lds_dwordx4 v0, s[64:65]
	s_waitcnt lgkmcnt(3)
	v_mfma_f32_16x16x32_bf16 v[48:51], v[214:217], v[162:165], v[48:51]
	v_mfma_f32_16x16x32_bf16 v[64:67], v[214:217], v[178:181], v[64:67]
	s_waitcnt lgkmcnt(2)
	v_mfma_f32_16x16x32_bf16 v[174:177], v[218:221], v[162:165], v[174:177]
	ds_read_b128 v[162:165], v16
	v_mfma_f32_16x16x32_bf16 v[170:173], v[218:221], v[178:181], v[170:173]
	ds_read_b128 v[178:181], v17
	s_waitcnt lgkmcnt(3)
	s_mov_b32 m0, s43
	v_mfma_f32_16x16x32_bf16 v[72:75], v[158:161], v[222:225], v[72:75]
	global_load_lds_dwordx4 v0, s[68:69]
	v_mfma_f32_16x16x32_bf16 v[76:79], v[166:169], v[222:225], v[76:79]
	v_mfma_f32_16x16x32_bf16 v[80:83], v[214:217], v[222:225], v[80:83]
	v_mfma_f32_16x16x32_bf16 v[32:35], v[218:221], v[222:225], v[32:35]
	ds_read_b128 v[222:225], v18
	s_waitcnt lgkmcnt(3)
	v_mfma_f32_16x16x32_bf16 v[88:91], v[158:161], v[226:229], v[88:91]
	s_mov_b32 m0, s44
	v_mfma_f32_16x16x32_bf16 v[92:95], v[166:169], v[226:229], v[92:95]
	global_load_lds_dwordx4 v2, s[64:65]
	v_mfma_f32_16x16x32_bf16 v[96:99], v[214:217], v[226:229], v[96:99]
	v_mfma_f32_16x16x32_bf16 v[36:39], v[218:221], v[226:229], v[36:39]
	ds_read_b128 v[226:229], v19
	s_waitcnt lgkmcnt(3)
	v_mfma_f32_16x16x32_bf16 v[104:107], v[158:161], v[162:165], v[104:107]
	s_waitcnt lgkmcnt(2)
	v_mfma_f32_16x16x32_bf16 v[116:119], v[158:161], v[178:181], v[116:119]
	s_waitcnt lgkmcnt(1)
	s_mov_b32 m0, s45
	v_mfma_f32_16x16x32_bf16 v[128:131], v[158:161], v[222:225], v[128:131]
	global_load_lds_dwordx4 v2, s[68:69]
	s_waitcnt lgkmcnt(0)
	v_mfma_f32_16x16x32_bf16 v[100:103], v[158:161], v[226:229], v[100:103]
	ds_read_b128 v[158:161], v20
	v_mfma_f32_16x16x32_bf16 v[108:111], v[166:169], v[162:165], v[108:111]
	v_mfma_f32_16x16x32_bf16 v[120:123], v[166:169], v[178:181], v[120:123]
	v_mfma_f32_16x16x32_bf16 v[132:135], v[166:169], v[222:225], v[132:135]
	s_mov_b32 m0, s46
	v_mfma_f32_16x16x32_bf16 v[140:143], v[166:169], v[226:229], v[140:143]
	global_load_lds_dwordx4 v4, s[64:65]
	ds_read_b128 v[166:169], v24
	v_mfma_f32_16x16x32_bf16 v[112:115], v[214:217], v[162:165], v[112:115]
	v_mfma_f32_16x16x32_bf16 v[52:55], v[218:221], v[162:165], v[52:55]
	ds_read_b128 v[162:165], v21
	v_mfma_f32_16x16x32_bf16 v[124:127], v[214:217], v[178:181], v[124:127]
	v_mfma_f32_16x16x32_bf16 v[68:71], v[218:221], v[178:181], v[68:71]
	ds_read_b128 v[178:181], v25
	s_mov_b32 m0, s47
	v_mfma_f32_16x16x32_bf16 v[136:139], v[214:217], v[222:225], v[136:139]
	global_load_lds_dwordx4 v4, s[68:69]
	v_mfma_f32_16x16x32_bf16 v[84:87], v[218:221], v[222:225], v[84:87]
	ds_read_b128 v[222:225], v26
	v_mfma_f32_16x16x32_bf16 v[150:153], v[214:217], v[226:229], v[150:153]
	ds_read_b128 v[214:217], v23
	v_mfma_f32_16x16x32_bf16 v[154:157], v[218:221], v[226:229], v[154:157]
	ds_read_b128 v[218:221], v22
	ds_read_b128 v[226:229], v27
	s_waitcnt lgkmcnt(6)
	v_mfma_f32_16x16x32_bf16 v[40:43], v[158:161], v[166:169], v[40:43]
	s_waitcnt lgkmcnt(5)
	s_mov_b32 m0, s49
	v_mfma_f32_16x16x32_bf16 v[44:47], v[162:165], v[166:169], v[44:47]
	global_load_lds_dwordx4 v146, s[64:65]
	s_waitcnt lgkmcnt(4)
	v_mfma_f32_16x16x32_bf16 v[56:59], v[158:161], v[178:181], v[56:59]
	v_mfma_f32_16x16x32_bf16 v[60:63], v[162:165], v[178:181], v[60:63]
	s_waitcnt lgkmcnt(3)
	v_mfma_f32_16x16x32_bf16 v[72:75], v[158:161], v[222:225], v[72:75]
	v_mfma_f32_16x16x32_bf16 v[76:79], v[162:165], v[222:225], v[76:79]
	s_waitcnt lgkmcnt(2)
	s_mov_b32 m0, s50
	v_mfma_f32_16x16x32_bf16 v[48:51], v[214:217], v[166:169], v[48:51]
	global_load_lds_dwordx4 v146, s[68:69]
	s_waitcnt lgkmcnt(1)
	v_mfma_f32_16x16x32_bf16 v[174:177], v[218:221], v[166:169], v[174:177]
	ds_read_b128 v[166:169], v28
	v_mfma_f32_16x16x32_bf16 v[64:67], v[214:217], v[178:181], v[64:67]
	v_mfma_f32_16x16x32_bf16 v[170:173], v[218:221], v[178:181], v[170:173]
	ds_read_b128 v[178:181], v29
	v_mfma_f32_16x16x32_bf16 v[80:83], v[214:217], v[222:225], v[80:83]
	v_mfma_f32_16x16x32_bf16 v[32:35], v[218:221], v[222:225], v[32:35]
	ds_read_b128 v[222:225], v30
	s_waitcnt lgkmcnt(3)
	v_mfma_f32_16x16x32_bf16 v[88:91], v[158:161], v[226:229], v[88:91]
	v_mfma_f32_16x16x32_bf16 v[92:95], v[162:165], v[226:229], v[92:95]
	v_mfma_f32_16x16x32_bf16 v[96:99], v[214:217], v[226:229], v[96:99]
	v_mfma_f32_16x16x32_bf16 v[36:39], v[218:221], v[226:229], v[36:39]
	ds_read_b128 v[226:229], v31
	s_waitcnt lgkmcnt(3)
	v_mfma_f32_16x16x32_bf16 v[104:107], v[158:161], v[166:169], v[104:107]
	v_mfma_f32_16x16x32_bf16 v[108:111], v[162:165], v[166:169], v[108:111]
	v_mfma_f32_16x16x32_bf16 v[112:115], v[214:217], v[166:169], v[112:115]
	v_mfma_f32_16x16x32_bf16 v[52:55], v[218:221], v[166:169], v[52:55]
	s_waitcnt lgkmcnt(2)
	v_mfma_f32_16x16x32_bf16 v[116:119], v[158:161], v[178:181], v[116:119]
	v_mfma_f32_16x16x32_bf16 v[120:123], v[162:165], v[178:181], v[120:123]
	v_mfma_f32_16x16x32_bf16 v[124:127], v[214:217], v[178:181], v[124:127]
	v_mfma_f32_16x16x32_bf16 v[68:71], v[218:221], v[178:181], v[68:71]
	s_waitcnt lgkmcnt(1)
	v_mfma_f32_16x16x32_bf16 v[128:131], v[158:161], v[222:225], v[128:131]
	v_mfma_f32_16x16x32_bf16 v[132:135], v[162:165], v[222:225], v[132:135]
	v_mfma_f32_16x16x32_bf16 v[136:139], v[214:217], v[222:225], v[136:139]
	v_mfma_f32_16x16x32_bf16 v[84:87], v[218:221], v[222:225], v[84:87]
	s_waitcnt lgkmcnt(0)
	v_mfma_f32_16x16x32_bf16 v[100:103], v[158:161], v[226:229], v[100:103]
	v_mfma_f32_16x16x32_bf16 v[140:143], v[162:165], v[226:229], v[140:143]
	v_mfma_f32_16x16x32_bf16 v[150:153], v[214:217], v[226:229], v[150:153]
	v_mfma_f32_16x16x32_bf16 v[154:157], v[218:221], v[226:229], v[154:157]
	s_add_u32 s64, s0, 0x1780
	s_addc_u32 s65, s1, 0
	s_add_u32 s68, s14, 0x1780
	s_waitcnt vmcnt(0)
	s_barrier
	s_addc_u32 s69, s15, 0
	ds_read_b128 v[158:161], v7 offset:32768
	ds_read_b128 v[162:165], v6
	ds_read_b128 v[166:169], v7 offset:34816
	ds_read_b128 v[178:181], v6 offset:2048
	ds_read_b128 v[214:217], v7 offset:36864
	ds_read_b128 v[218:221], v7 offset:38912
	ds_read_b128 v[222:225], v6 offset:4096
	ds_read_b128 v[226:229], v6 offset:6144
	s_waitcnt lgkmcnt(6)
	v_mfma_f32_16x16x32_bf16 v[40:43], v[158:161], v[162:165], v[40:43]
	s_waitcnt lgkmcnt(5)
	v_mfma_f32_16x16x32_bf16 v[44:47], v[166:169], v[162:165], v[44:47]
	s_waitcnt lgkmcnt(4)
	v_mfma_f32_16x16x32_bf16 v[56:59], v[158:161], v[178:181], v[56:59]
	s_mov_b32 m0, s52
	v_mfma_f32_16x16x32_bf16 v[60:63], v[166:169], v[178:181], v[60:63]
	global_load_lds_dwordx4 v0, s[64:65]
	s_waitcnt lgkmcnt(3)
	v_mfma_f32_16x16x32_bf16 v[48:51], v[214:217], v[162:165], v[48:51]
	v_mfma_f32_16x16x32_bf16 v[64:67], v[214:217], v[178:181], v[64:67]
	s_waitcnt lgkmcnt(2)
	v_mfma_f32_16x16x32_bf16 v[174:177], v[218:221], v[162:165], v[174:177]
	ds_read_b128 v[162:165], v6 offset:8192
	v_mfma_f32_16x16x32_bf16 v[170:173], v[218:221], v[178:181], v[170:173]
	ds_read_b128 v[178:181], v6 offset:10240
	s_waitcnt lgkmcnt(3)
	s_mov_b32 m0, s51
	v_mfma_f32_16x16x32_bf16 v[72:75], v[158:161], v[222:225], v[72:75]
	global_load_lds_dwordx4 v0, s[68:69]
	v_mfma_f32_16x16x32_bf16 v[76:79], v[166:169], v[222:225], v[76:79]
	v_mfma_f32_16x16x32_bf16 v[80:83], v[214:217], v[222:225], v[80:83]
	v_mfma_f32_16x16x32_bf16 v[32:35], v[218:221], v[222:225], v[32:35]
	ds_read_b128 v[222:225], v6 offset:12288
	s_waitcnt lgkmcnt(3)
	v_mfma_f32_16x16x32_bf16 v[88:91], v[158:161], v[226:229], v[88:91]
	s_mov_b32 m0, s53
	v_mfma_f32_16x16x32_bf16 v[92:95], v[166:169], v[226:229], v[92:95]
	global_load_lds_dwordx4 v2, s[64:65]
	v_mfma_f32_16x16x32_bf16 v[96:99], v[214:217], v[226:229], v[96:99]
	v_mfma_f32_16x16x32_bf16 v[36:39], v[218:221], v[226:229], v[36:39]
	ds_read_b128 v[226:229], v6 offset:14336
	s_waitcnt lgkmcnt(3)
	v_mfma_f32_16x16x32_bf16 v[104:107], v[158:161], v[162:165], v[104:107]
	s_waitcnt lgkmcnt(2)
	v_mfma_f32_16x16x32_bf16 v[116:119], v[158:161], v[178:181], v[116:119]
	s_waitcnt lgkmcnt(1)
	s_mov_b32 m0, s54
	v_mfma_f32_16x16x32_bf16 v[128:131], v[158:161], v[222:225], v[128:131]
	global_load_lds_dwordx4 v2, s[68:69]
	s_waitcnt lgkmcnt(0)
	v_mfma_f32_16x16x32_bf16 v[100:103], v[158:161], v[226:229], v[100:103]
	ds_read_b128 v[158:161], v7 offset:33792
	v_mfma_f32_16x16x32_bf16 v[108:111], v[166:169], v[162:165], v[108:111]
	v_mfma_f32_16x16x32_bf16 v[120:123], v[166:169], v[178:181], v[120:123]
	v_mfma_f32_16x16x32_bf16 v[132:135], v[166:169], v[222:225], v[132:135]
	s_mov_b32 m0, s55
	v_mfma_f32_16x16x32_bf16 v[140:143], v[166:169], v[226:229], v[140:143]
	global_load_lds_dwordx4 v4, s[64:65]
	ds_read_b128 v[166:169], v6 offset:1024
	v_mfma_f32_16x16x32_bf16 v[112:115], v[214:217], v[162:165], v[112:115]
	v_mfma_f32_16x16x32_bf16 v[52:55], v[218:221], v[162:165], v[52:55]
	ds_read_b128 v[162:165], v7 offset:35840
	v_mfma_f32_16x16x32_bf16 v[124:127], v[214:217], v[178:181], v[124:127]
	v_mfma_f32_16x16x32_bf16 v[68:71], v[218:221], v[178:181], v[68:71]
	ds_read_b128 v[178:181], v6 offset:3072
	s_mov_b32 m0, s58
	v_mfma_f32_16x16x32_bf16 v[136:139], v[214:217], v[222:225], v[136:139]
	global_load_lds_dwordx4 v4, s[68:69]
	v_mfma_f32_16x16x32_bf16 v[84:87], v[218:221], v[222:225], v[84:87]
	ds_read_b128 v[222:225], v6 offset:5120
	v_mfma_f32_16x16x32_bf16 v[150:153], v[214:217], v[226:229], v[150:153]
	ds_read_b128 v[214:217], v7 offset:37888
	v_mfma_f32_16x16x32_bf16 v[154:157], v[218:221], v[226:229], v[154:157]
	ds_read_b128 v[218:221], v7 offset:39936
	ds_read_b128 v[226:229], v6 offset:7168
	s_waitcnt lgkmcnt(6)
	v_mfma_f32_16x16x32_bf16 v[40:43], v[158:161], v[166:169], v[40:43]
	s_waitcnt lgkmcnt(5)
	s_mov_b32 m0, s62
	v_mfma_f32_16x16x32_bf16 v[44:47], v[162:165], v[166:169], v[44:47]
	global_load_lds_dwordx4 v146, s[64:65]
	s_waitcnt lgkmcnt(4)
	v_mfma_f32_16x16x32_bf16 v[56:59], v[158:161], v[178:181], v[56:59]
	v_mfma_f32_16x16x32_bf16 v[60:63], v[162:165], v[178:181], v[60:63]
	s_waitcnt lgkmcnt(3)
	v_mfma_f32_16x16x32_bf16 v[72:75], v[158:161], v[222:225], v[72:75]
	v_mfma_f32_16x16x32_bf16 v[76:79], v[162:165], v[222:225], v[76:79]
	s_waitcnt lgkmcnt(2)
	s_mov_b32 m0, s63
	v_mfma_f32_16x16x32_bf16 v[48:51], v[214:217], v[166:169], v[48:51]
	global_load_lds_dwordx4 v146, s[68:69]
	s_waitcnt lgkmcnt(1)
	v_mfma_f32_16x16x32_bf16 v[174:177], v[218:221], v[166:169], v[174:177]
	ds_read_b128 v[166:169], v6 offset:9216
	v_mfma_f32_16x16x32_bf16 v[64:67], v[214:217], v[178:181], v[64:67]
	v_mfma_f32_16x16x32_bf16 v[170:173], v[218:221], v[178:181], v[170:173]
	ds_read_b128 v[178:181], v6 offset:11264
	v_mfma_f32_16x16x32_bf16 v[80:83], v[214:217], v[222:225], v[80:83]
	v_mfma_f32_16x16x32_bf16 v[32:35], v[218:221], v[222:225], v[32:35]
	ds_read_b128 v[222:225], v6 offset:13312
	s_waitcnt lgkmcnt(3)
	v_mfma_f32_16x16x32_bf16 v[88:91], v[158:161], v[226:229], v[88:91]
	v_mfma_f32_16x16x32_bf16 v[92:95], v[162:165], v[226:229], v[92:95]
	v_mfma_f32_16x16x32_bf16 v[96:99], v[214:217], v[226:229], v[96:99]
	v_mfma_f32_16x16x32_bf16 v[36:39], v[218:221], v[226:229], v[36:39]
	ds_read_b128 v[226:229], v6 offset:15360
	s_waitcnt lgkmcnt(3)
	v_mfma_f32_16x16x32_bf16 v[104:107], v[158:161], v[166:169], v[104:107]
	v_mfma_f32_16x16x32_bf16 v[108:111], v[162:165], v[166:169], v[108:111]
	v_mfma_f32_16x16x32_bf16 v[112:115], v[214:217], v[166:169], v[112:115]
	v_mfma_f32_16x16x32_bf16 v[52:55], v[218:221], v[166:169], v[52:55]
	s_waitcnt lgkmcnt(2)
	v_mfma_f32_16x16x32_bf16 v[116:119], v[158:161], v[178:181], v[116:119]
	v_mfma_f32_16x16x32_bf16 v[120:123], v[162:165], v[178:181], v[120:123]
	v_mfma_f32_16x16x32_bf16 v[124:127], v[214:217], v[178:181], v[124:127]
	v_mfma_f32_16x16x32_bf16 v[68:71], v[218:221], v[178:181], v[68:71]
	s_waitcnt lgkmcnt(1)
	v_mfma_f32_16x16x32_bf16 v[128:131], v[158:161], v[222:225], v[128:131]
	v_mfma_f32_16x16x32_bf16 v[132:135], v[162:165], v[222:225], v[132:135]
	v_mfma_f32_16x16x32_bf16 v[136:139], v[214:217], v[222:225], v[136:139]
	v_mfma_f32_16x16x32_bf16 v[84:87], v[218:221], v[222:225], v[84:87]
	s_waitcnt lgkmcnt(0)
	v_mfma_f32_16x16x32_bf16 v[100:103], v[158:161], v[226:229], v[100:103]
	v_mfma_f32_16x16x32_bf16 v[140:143], v[162:165], v[226:229], v[140:143]
	v_mfma_f32_16x16x32_bf16 v[150:153], v[214:217], v[226:229], v[150:153]
	v_mfma_f32_16x16x32_bf16 v[154:157], v[218:221], v[226:229], v[154:157]
	s_add_u32 s64, s0, 0x1800
	s_addc_u32 s65, s1, 0
	s_add_u32 s68, s14, 0x1800
	s_waitcnt vmcnt(0)
	s_barrier
	s_addc_u32 s69, s15, 0
	ds_read_b128 v[158:161], v8
	ds_read_b128 v[162:165], v12
	ds_read_b128 v[166:169], v9
	ds_read_b128 v[178:181], v13
	ds_read_b128 v[214:217], v11
	ds_read_b128 v[218:221], v10
	ds_read_b128 v[222:225], v14
	ds_read_b128 v[226:229], v15
	s_waitcnt lgkmcnt(6)
	v_mfma_f32_16x16x32_bf16 v[40:43], v[158:161], v[162:165], v[40:43]
	s_waitcnt lgkmcnt(5)
	v_mfma_f32_16x16x32_bf16 v[44:47], v[166:169], v[162:165], v[44:47]
	s_waitcnt lgkmcnt(4)
	v_mfma_f32_16x16x32_bf16 v[56:59], v[158:161], v[178:181], v[56:59]
	s_mov_b32 m0, s42
	v_mfma_f32_16x16x32_bf16 v[60:63], v[166:169], v[178:181], v[60:63]
	global_load_lds_dwordx4 v0, s[64:65]
	s_waitcnt lgkmcnt(3)
	v_mfma_f32_16x16x32_bf16 v[48:51], v[214:217], v[162:165], v[48:51]
	v_mfma_f32_16x16x32_bf16 v[64:67], v[214:217], v[178:181], v[64:67]
	s_waitcnt lgkmcnt(2)
	v_mfma_f32_16x16x32_bf16 v[174:177], v[218:221], v[162:165], v[174:177]
	ds_read_b128 v[162:165], v16
	v_mfma_f32_16x16x32_bf16 v[170:173], v[218:221], v[178:181], v[170:173]
	ds_read_b128 v[178:181], v17
	s_waitcnt lgkmcnt(3)
	s_mov_b32 m0, s43
	v_mfma_f32_16x16x32_bf16 v[72:75], v[158:161], v[222:225], v[72:75]
	global_load_lds_dwordx4 v0, s[68:69]
	v_mfma_f32_16x16x32_bf16 v[76:79], v[166:169], v[222:225], v[76:79]
	v_mfma_f32_16x16x32_bf16 v[80:83], v[214:217], v[222:225], v[80:83]
	v_mfma_f32_16x16x32_bf16 v[32:35], v[218:221], v[222:225], v[32:35]
	ds_read_b128 v[222:225], v18
	s_waitcnt lgkmcnt(3)
	v_mfma_f32_16x16x32_bf16 v[88:91], v[158:161], v[226:229], v[88:91]
	s_mov_b32 m0, s44
	v_mfma_f32_16x16x32_bf16 v[92:95], v[166:169], v[226:229], v[92:95]
	global_load_lds_dwordx4 v2, s[64:65]
	v_mfma_f32_16x16x32_bf16 v[96:99], v[214:217], v[226:229], v[96:99]
	v_mfma_f32_16x16x32_bf16 v[36:39], v[218:221], v[226:229], v[36:39]
	ds_read_b128 v[226:229], v19
	s_waitcnt lgkmcnt(3)
	v_mfma_f32_16x16x32_bf16 v[104:107], v[158:161], v[162:165], v[104:107]
	s_waitcnt lgkmcnt(2)
	v_mfma_f32_16x16x32_bf16 v[116:119], v[158:161], v[178:181], v[116:119]
	s_waitcnt lgkmcnt(1)
	s_mov_b32 m0, s45
	v_mfma_f32_16x16x32_bf16 v[128:131], v[158:161], v[222:225], v[128:131]
	global_load_lds_dwordx4 v2, s[68:69]
	s_waitcnt lgkmcnt(0)
	v_mfma_f32_16x16x32_bf16 v[100:103], v[158:161], v[226:229], v[100:103]
	ds_read_b128 v[158:161], v20
	v_mfma_f32_16x16x32_bf16 v[108:111], v[166:169], v[162:165], v[108:111]
	v_mfma_f32_16x16x32_bf16 v[120:123], v[166:169], v[178:181], v[120:123]
	v_mfma_f32_16x16x32_bf16 v[132:135], v[166:169], v[222:225], v[132:135]
	s_mov_b32 m0, s46
	v_mfma_f32_16x16x32_bf16 v[140:143], v[166:169], v[226:229], v[140:143]
	global_load_lds_dwordx4 v4, s[64:65]
	ds_read_b128 v[166:169], v24
	v_mfma_f32_16x16x32_bf16 v[112:115], v[214:217], v[162:165], v[112:115]
	v_mfma_f32_16x16x32_bf16 v[52:55], v[218:221], v[162:165], v[52:55]
	ds_read_b128 v[162:165], v21
	v_mfma_f32_16x16x32_bf16 v[124:127], v[214:217], v[178:181], v[124:127]
	v_mfma_f32_16x16x32_bf16 v[68:71], v[218:221], v[178:181], v[68:71]
	ds_read_b128 v[178:181], v25
	s_mov_b32 m0, s47
	v_mfma_f32_16x16x32_bf16 v[136:139], v[214:217], v[222:225], v[136:139]
	global_load_lds_dwordx4 v4, s[68:69]
	v_mfma_f32_16x16x32_bf16 v[84:87], v[218:221], v[222:225], v[84:87]
	ds_read_b128 v[222:225], v26
	v_mfma_f32_16x16x32_bf16 v[150:153], v[214:217], v[226:229], v[150:153]
	ds_read_b128 v[214:217], v23
	v_mfma_f32_16x16x32_bf16 v[154:157], v[218:221], v[226:229], v[154:157]
	ds_read_b128 v[218:221], v22
	ds_read_b128 v[226:229], v27
	s_waitcnt lgkmcnt(6)
	v_mfma_f32_16x16x32_bf16 v[40:43], v[158:161], v[166:169], v[40:43]
	s_waitcnt lgkmcnt(5)
	s_mov_b32 m0, s49
	v_mfma_f32_16x16x32_bf16 v[44:47], v[162:165], v[166:169], v[44:47]
	global_load_lds_dwordx4 v146, s[64:65]
	s_waitcnt lgkmcnt(4)
	v_mfma_f32_16x16x32_bf16 v[56:59], v[158:161], v[178:181], v[56:59]
	v_mfma_f32_16x16x32_bf16 v[60:63], v[162:165], v[178:181], v[60:63]
	s_waitcnt lgkmcnt(3)
	v_mfma_f32_16x16x32_bf16 v[72:75], v[158:161], v[222:225], v[72:75]
	v_mfma_f32_16x16x32_bf16 v[76:79], v[162:165], v[222:225], v[76:79]
	s_waitcnt lgkmcnt(2)
	s_mov_b32 m0, s50
	v_mfma_f32_16x16x32_bf16 v[48:51], v[214:217], v[166:169], v[48:51]
	global_load_lds_dwordx4 v146, s[68:69]
	s_waitcnt lgkmcnt(1)
	v_mfma_f32_16x16x32_bf16 v[174:177], v[218:221], v[166:169], v[174:177]
	ds_read_b128 v[166:169], v28
	v_mfma_f32_16x16x32_bf16 v[64:67], v[214:217], v[178:181], v[64:67]
	v_mfma_f32_16x16x32_bf16 v[170:173], v[218:221], v[178:181], v[170:173]
	ds_read_b128 v[178:181], v29
	v_mfma_f32_16x16x32_bf16 v[80:83], v[214:217], v[222:225], v[80:83]
	v_mfma_f32_16x16x32_bf16 v[32:35], v[218:221], v[222:225], v[32:35]
	ds_read_b128 v[222:225], v30
	s_waitcnt lgkmcnt(3)
	v_mfma_f32_16x16x32_bf16 v[88:91], v[158:161], v[226:229], v[88:91]
	v_mfma_f32_16x16x32_bf16 v[92:95], v[162:165], v[226:229], v[92:95]
	v_mfma_f32_16x16x32_bf16 v[96:99], v[214:217], v[226:229], v[96:99]
	v_mfma_f32_16x16x32_bf16 v[36:39], v[218:221], v[226:229], v[36:39]
	ds_read_b128 v[226:229], v31
	s_waitcnt lgkmcnt(3)
	v_mfma_f32_16x16x32_bf16 v[104:107], v[158:161], v[166:169], v[104:107]
	v_mfma_f32_16x16x32_bf16 v[108:111], v[162:165], v[166:169], v[108:111]
	v_mfma_f32_16x16x32_bf16 v[112:115], v[214:217], v[166:169], v[112:115]
	v_mfma_f32_16x16x32_bf16 v[52:55], v[218:221], v[166:169], v[52:55]
	s_waitcnt lgkmcnt(2)
	v_mfma_f32_16x16x32_bf16 v[116:119], v[158:161], v[178:181], v[116:119]
	v_mfma_f32_16x16x32_bf16 v[120:123], v[162:165], v[178:181], v[120:123]
	v_mfma_f32_16x16x32_bf16 v[124:127], v[214:217], v[178:181], v[124:127]
	v_mfma_f32_16x16x32_bf16 v[68:71], v[218:221], v[178:181], v[68:71]
	s_waitcnt lgkmcnt(1)
	v_mfma_f32_16x16x32_bf16 v[128:131], v[158:161], v[222:225], v[128:131]
	v_mfma_f32_16x16x32_bf16 v[132:135], v[162:165], v[222:225], v[132:135]
	v_mfma_f32_16x16x32_bf16 v[136:139], v[214:217], v[222:225], v[136:139]
	v_mfma_f32_16x16x32_bf16 v[84:87], v[218:221], v[222:225], v[84:87]
	s_waitcnt lgkmcnt(0)
	v_mfma_f32_16x16x32_bf16 v[100:103], v[158:161], v[226:229], v[100:103]
	v_mfma_f32_16x16x32_bf16 v[140:143], v[162:165], v[226:229], v[140:143]
	v_mfma_f32_16x16x32_bf16 v[150:153], v[214:217], v[226:229], v[150:153]
	v_mfma_f32_16x16x32_bf16 v[154:157], v[218:221], v[226:229], v[154:157]
	s_add_u32 s64, s0, 0x1880
	s_addc_u32 s65, s1, 0
	s_add_u32 s68, s14, 0x1880
	s_waitcnt vmcnt(0)
	s_barrier
	s_addc_u32 s69, s15, 0
	ds_read_b128 v[158:161], v7 offset:32768
	ds_read_b128 v[162:165], v6
	ds_read_b128 v[166:169], v7 offset:34816
	ds_read_b128 v[178:181], v6 offset:2048
	ds_read_b128 v[214:217], v7 offset:36864
	ds_read_b128 v[218:221], v7 offset:38912
	ds_read_b128 v[222:225], v6 offset:4096
	ds_read_b128 v[226:229], v6 offset:6144
	s_waitcnt lgkmcnt(6)
	v_mfma_f32_16x16x32_bf16 v[40:43], v[158:161], v[162:165], v[40:43]
	s_waitcnt lgkmcnt(5)
	v_mfma_f32_16x16x32_bf16 v[44:47], v[166:169], v[162:165], v[44:47]
	s_waitcnt lgkmcnt(4)
	v_mfma_f32_16x16x32_bf16 v[56:59], v[158:161], v[178:181], v[56:59]
	s_mov_b32 m0, s52
	v_mfma_f32_16x16x32_bf16 v[60:63], v[166:169], v[178:181], v[60:63]
	global_load_lds_dwordx4 v0, s[64:65]
	s_waitcnt lgkmcnt(3)
	v_mfma_f32_16x16x32_bf16 v[48:51], v[214:217], v[162:165], v[48:51]
	v_mfma_f32_16x16x32_bf16 v[64:67], v[214:217], v[178:181], v[64:67]
	s_waitcnt lgkmcnt(2)
	v_mfma_f32_16x16x32_bf16 v[174:177], v[218:221], v[162:165], v[174:177]
	ds_read_b128 v[162:165], v6 offset:8192
	v_mfma_f32_16x16x32_bf16 v[170:173], v[218:221], v[178:181], v[170:173]
	ds_read_b128 v[178:181], v6 offset:10240
	s_waitcnt lgkmcnt(3)
	s_mov_b32 m0, s51
	v_mfma_f32_16x16x32_bf16 v[72:75], v[158:161], v[222:225], v[72:75]
	global_load_lds_dwordx4 v0, s[68:69]
	v_mfma_f32_16x16x32_bf16 v[76:79], v[166:169], v[222:225], v[76:79]
	v_mfma_f32_16x16x32_bf16 v[80:83], v[214:217], v[222:225], v[80:83]
	v_mfma_f32_16x16x32_bf16 v[32:35], v[218:221], v[222:225], v[32:35]
	ds_read_b128 v[222:225], v6 offset:12288
	s_waitcnt lgkmcnt(3)
	v_mfma_f32_16x16x32_bf16 v[88:91], v[158:161], v[226:229], v[88:91]
	s_mov_b32 m0, s53
	v_mfma_f32_16x16x32_bf16 v[92:95], v[166:169], v[226:229], v[92:95]
	global_load_lds_dwordx4 v2, s[64:65]
	v_mfma_f32_16x16x32_bf16 v[96:99], v[214:217], v[226:229], v[96:99]
	v_mfma_f32_16x16x32_bf16 v[36:39], v[218:221], v[226:229], v[36:39]
	ds_read_b128 v[226:229], v6 offset:14336
	s_waitcnt lgkmcnt(3)
	v_mfma_f32_16x16x32_bf16 v[104:107], v[158:161], v[162:165], v[104:107]
	s_waitcnt lgkmcnt(2)
	v_mfma_f32_16x16x32_bf16 v[116:119], v[158:161], v[178:181], v[116:119]
	s_waitcnt lgkmcnt(1)
	s_mov_b32 m0, s54
	v_mfma_f32_16x16x32_bf16 v[128:131], v[158:161], v[222:225], v[128:131]
	global_load_lds_dwordx4 v2, s[68:69]
	s_waitcnt lgkmcnt(0)
	v_mfma_f32_16x16x32_bf16 v[100:103], v[158:161], v[226:229], v[100:103]
	ds_read_b128 v[158:161], v7 offset:33792
	v_mfma_f32_16x16x32_bf16 v[108:111], v[166:169], v[162:165], v[108:111]
	v_mfma_f32_16x16x32_bf16 v[120:123], v[166:169], v[178:181], v[120:123]
	v_mfma_f32_16x16x32_bf16 v[132:135], v[166:169], v[222:225], v[132:135]
	s_mov_b32 m0, s55
	v_mfma_f32_16x16x32_bf16 v[140:143], v[166:169], v[226:229], v[140:143]
	global_load_lds_dwordx4 v4, s[64:65]
	ds_read_b128 v[166:169], v6 offset:1024
	v_mfma_f32_16x16x32_bf16 v[112:115], v[214:217], v[162:165], v[112:115]
	v_mfma_f32_16x16x32_bf16 v[52:55], v[218:221], v[162:165], v[52:55]
	ds_read_b128 v[162:165], v7 offset:35840
	v_mfma_f32_16x16x32_bf16 v[124:127], v[214:217], v[178:181], v[124:127]
	v_mfma_f32_16x16x32_bf16 v[68:71], v[218:221], v[178:181], v[68:71]
	ds_read_b128 v[178:181], v6 offset:3072
	s_mov_b32 m0, s58
	v_mfma_f32_16x16x32_bf16 v[136:139], v[214:217], v[222:225], v[136:139]
	global_load_lds_dwordx4 v4, s[68:69]
	v_mfma_f32_16x16x32_bf16 v[84:87], v[218:221], v[222:225], v[84:87]
	ds_read_b128 v[222:225], v6 offset:5120
	v_mfma_f32_16x16x32_bf16 v[150:153], v[214:217], v[226:229], v[150:153]
	ds_read_b128 v[214:217], v7 offset:37888
	v_mfma_f32_16x16x32_bf16 v[154:157], v[218:221], v[226:229], v[154:157]
	ds_read_b128 v[218:221], v7 offset:39936
	ds_read_b128 v[226:229], v6 offset:7168
	s_waitcnt lgkmcnt(6)
	v_mfma_f32_16x16x32_bf16 v[40:43], v[158:161], v[166:169], v[40:43]
	s_waitcnt lgkmcnt(5)
	s_mov_b32 m0, s62
	v_mfma_f32_16x16x32_bf16 v[44:47], v[162:165], v[166:169], v[44:47]
	global_load_lds_dwordx4 v146, s[64:65]
	s_waitcnt lgkmcnt(4)
	v_mfma_f32_16x16x32_bf16 v[56:59], v[158:161], v[178:181], v[56:59]
	v_mfma_f32_16x16x32_bf16 v[60:63], v[162:165], v[178:181], v[60:63]
	s_waitcnt lgkmcnt(3)
	v_mfma_f32_16x16x32_bf16 v[72:75], v[158:161], v[222:225], v[72:75]
	v_mfma_f32_16x16x32_bf16 v[76:79], v[162:165], v[222:225], v[76:79]
	s_waitcnt lgkmcnt(2)
	s_mov_b32 m0, s63
	v_mfma_f32_16x16x32_bf16 v[48:51], v[214:217], v[166:169], v[48:51]
	global_load_lds_dwordx4 v146, s[68:69]
	s_waitcnt lgkmcnt(1)
	v_mfma_f32_16x16x32_bf16 v[174:177], v[218:221], v[166:169], v[174:177]
	ds_read_b128 v[166:169], v6 offset:9216
	v_mfma_f32_16x16x32_bf16 v[64:67], v[214:217], v[178:181], v[64:67]
	v_mfma_f32_16x16x32_bf16 v[170:173], v[218:221], v[178:181], v[170:173]
	ds_read_b128 v[178:181], v6 offset:11264
	v_mfma_f32_16x16x32_bf16 v[80:83], v[214:217], v[222:225], v[80:83]
	v_mfma_f32_16x16x32_bf16 v[32:35], v[218:221], v[222:225], v[32:35]
	ds_read_b128 v[222:225], v6 offset:13312
	s_waitcnt lgkmcnt(3)
	v_mfma_f32_16x16x32_bf16 v[88:91], v[158:161], v[226:229], v[88:91]
	v_mfma_f32_16x16x32_bf16 v[92:95], v[162:165], v[226:229], v[92:95]
	v_mfma_f32_16x16x32_bf16 v[96:99], v[214:217], v[226:229], v[96:99]
	v_mfma_f32_16x16x32_bf16 v[36:39], v[218:221], v[226:229], v[36:39]
	ds_read_b128 v[226:229], v6 offset:15360
	s_waitcnt lgkmcnt(3)
	v_mfma_f32_16x16x32_bf16 v[104:107], v[158:161], v[166:169], v[104:107]
	v_mfma_f32_16x16x32_bf16 v[108:111], v[162:165], v[166:169], v[108:111]
	v_mfma_f32_16x16x32_bf16 v[112:115], v[214:217], v[166:169], v[112:115]
	v_mfma_f32_16x16x32_bf16 v[52:55], v[218:221], v[166:169], v[52:55]
	s_waitcnt lgkmcnt(2)
	v_mfma_f32_16x16x32_bf16 v[116:119], v[158:161], v[178:181], v[116:119]
	v_mfma_f32_16x16x32_bf16 v[120:123], v[162:165], v[178:181], v[120:123]
	v_mfma_f32_16x16x32_bf16 v[124:127], v[214:217], v[178:181], v[124:127]
	v_mfma_f32_16x16x32_bf16 v[68:71], v[218:221], v[178:181], v[68:71]
	s_waitcnt lgkmcnt(1)
	v_mfma_f32_16x16x32_bf16 v[128:131], v[158:161], v[222:225], v[128:131]
	v_mfma_f32_16x16x32_bf16 v[132:135], v[162:165], v[222:225], v[132:135]
	v_mfma_f32_16x16x32_bf16 v[136:139], v[214:217], v[222:225], v[136:139]
	v_mfma_f32_16x16x32_bf16 v[84:87], v[218:221], v[222:225], v[84:87]
	s_waitcnt lgkmcnt(0)
	v_mfma_f32_16x16x32_bf16 v[100:103], v[158:161], v[226:229], v[100:103]
	v_mfma_f32_16x16x32_bf16 v[140:143], v[162:165], v[226:229], v[140:143]
	v_mfma_f32_16x16x32_bf16 v[150:153], v[214:217], v[226:229], v[150:153]
	v_mfma_f32_16x16x32_bf16 v[154:157], v[218:221], v[226:229], v[154:157]
	s_add_u32 s64, s0, 0x1900
	s_addc_u32 s65, s1, 0
	s_add_u32 s68, s14, 0x1900
	s_waitcnt vmcnt(0)
	s_barrier
	s_addc_u32 s69, s15, 0
	ds_read_b128 v[158:161], v8
	ds_read_b128 v[162:165], v12
	ds_read_b128 v[166:169], v9
	ds_read_b128 v[178:181], v13
	ds_read_b128 v[214:217], v11
	ds_read_b128 v[218:221], v10
	ds_read_b128 v[222:225], v14
	ds_read_b128 v[226:229], v15
	s_waitcnt lgkmcnt(6)
	v_mfma_f32_16x16x32_bf16 v[40:43], v[158:161], v[162:165], v[40:43]
	s_waitcnt lgkmcnt(5)
	v_mfma_f32_16x16x32_bf16 v[44:47], v[166:169], v[162:165], v[44:47]
	s_waitcnt lgkmcnt(4)
	v_mfma_f32_16x16x32_bf16 v[56:59], v[158:161], v[178:181], v[56:59]
	s_mov_b32 m0, s42
	v_mfma_f32_16x16x32_bf16 v[60:63], v[166:169], v[178:181], v[60:63]
	global_load_lds_dwordx4 v0, s[64:65]
	s_waitcnt lgkmcnt(3)
	v_mfma_f32_16x16x32_bf16 v[48:51], v[214:217], v[162:165], v[48:51]
	v_mfma_f32_16x16x32_bf16 v[64:67], v[214:217], v[178:181], v[64:67]
	s_waitcnt lgkmcnt(2)
	v_mfma_f32_16x16x32_bf16 v[174:177], v[218:221], v[162:165], v[174:177]
	ds_read_b128 v[162:165], v16
	v_mfma_f32_16x16x32_bf16 v[170:173], v[218:221], v[178:181], v[170:173]
	ds_read_b128 v[178:181], v17
	s_waitcnt lgkmcnt(3)
	s_mov_b32 m0, s43
	v_mfma_f32_16x16x32_bf16 v[72:75], v[158:161], v[222:225], v[72:75]
	global_load_lds_dwordx4 v0, s[68:69]
	v_mfma_f32_16x16x32_bf16 v[76:79], v[166:169], v[222:225], v[76:79]
	v_mfma_f32_16x16x32_bf16 v[80:83], v[214:217], v[222:225], v[80:83]
	v_mfma_f32_16x16x32_bf16 v[32:35], v[218:221], v[222:225], v[32:35]
	ds_read_b128 v[222:225], v18
	s_waitcnt lgkmcnt(3)
	v_mfma_f32_16x16x32_bf16 v[88:91], v[158:161], v[226:229], v[88:91]
	s_mov_b32 m0, s44
	v_mfma_f32_16x16x32_bf16 v[92:95], v[166:169], v[226:229], v[92:95]
	global_load_lds_dwordx4 v2, s[64:65]
	v_mfma_f32_16x16x32_bf16 v[96:99], v[214:217], v[226:229], v[96:99]
	v_mfma_f32_16x16x32_bf16 v[36:39], v[218:221], v[226:229], v[36:39]
	ds_read_b128 v[226:229], v19
	s_waitcnt lgkmcnt(3)
	v_mfma_f32_16x16x32_bf16 v[104:107], v[158:161], v[162:165], v[104:107]
	s_waitcnt lgkmcnt(2)
	v_mfma_f32_16x16x32_bf16 v[116:119], v[158:161], v[178:181], v[116:119]
	s_waitcnt lgkmcnt(1)
	s_mov_b32 m0, s45
	v_mfma_f32_16x16x32_bf16 v[128:131], v[158:161], v[222:225], v[128:131]
	global_load_lds_dwordx4 v2, s[68:69]
	s_waitcnt lgkmcnt(0)
	v_mfma_f32_16x16x32_bf16 v[100:103], v[158:161], v[226:229], v[100:103]
	ds_read_b128 v[158:161], v20
	v_mfma_f32_16x16x32_bf16 v[108:111], v[166:169], v[162:165], v[108:111]
	v_mfma_f32_16x16x32_bf16 v[120:123], v[166:169], v[178:181], v[120:123]
	v_mfma_f32_16x16x32_bf16 v[132:135], v[166:169], v[222:225], v[132:135]
	s_mov_b32 m0, s46
	v_mfma_f32_16x16x32_bf16 v[140:143], v[166:169], v[226:229], v[140:143]
	global_load_lds_dwordx4 v4, s[64:65]
	ds_read_b128 v[166:169], v24
	v_mfma_f32_16x16x32_bf16 v[112:115], v[214:217], v[162:165], v[112:115]
	v_mfma_f32_16x16x32_bf16 v[52:55], v[218:221], v[162:165], v[52:55]
	ds_read_b128 v[162:165], v21
	v_mfma_f32_16x16x32_bf16 v[124:127], v[214:217], v[178:181], v[124:127]
	v_mfma_f32_16x16x32_bf16 v[68:71], v[218:221], v[178:181], v[68:71]
	ds_read_b128 v[178:181], v25
	s_mov_b32 m0, s47
	v_mfma_f32_16x16x32_bf16 v[136:139], v[214:217], v[222:225], v[136:139]
	global_load_lds_dwordx4 v4, s[68:69]
	v_mfma_f32_16x16x32_bf16 v[84:87], v[218:221], v[222:225], v[84:87]
	ds_read_b128 v[222:225], v26
	v_mfma_f32_16x16x32_bf16 v[150:153], v[214:217], v[226:229], v[150:153]
	ds_read_b128 v[214:217], v23
	v_mfma_f32_16x16x32_bf16 v[154:157], v[218:221], v[226:229], v[154:157]
	ds_read_b128 v[218:221], v22
	ds_read_b128 v[226:229], v27
	s_waitcnt lgkmcnt(6)
	v_mfma_f32_16x16x32_bf16 v[40:43], v[158:161], v[166:169], v[40:43]
	s_waitcnt lgkmcnt(5)
	s_mov_b32 m0, s49
	v_mfma_f32_16x16x32_bf16 v[44:47], v[162:165], v[166:169], v[44:47]
	global_load_lds_dwordx4 v146, s[64:65]
	s_waitcnt lgkmcnt(4)
	v_mfma_f32_16x16x32_bf16 v[56:59], v[158:161], v[178:181], v[56:59]
	v_mfma_f32_16x16x32_bf16 v[60:63], v[162:165], v[178:181], v[60:63]
	s_waitcnt lgkmcnt(3)
	v_mfma_f32_16x16x32_bf16 v[72:75], v[158:161], v[222:225], v[72:75]
	v_mfma_f32_16x16x32_bf16 v[76:79], v[162:165], v[222:225], v[76:79]
	s_waitcnt lgkmcnt(2)
	s_mov_b32 m0, s50
	v_mfma_f32_16x16x32_bf16 v[48:51], v[214:217], v[166:169], v[48:51]
	global_load_lds_dwordx4 v146, s[68:69]
	s_waitcnt lgkmcnt(1)
	v_mfma_f32_16x16x32_bf16 v[174:177], v[218:221], v[166:169], v[174:177]
	ds_read_b128 v[166:169], v28
	v_mfma_f32_16x16x32_bf16 v[64:67], v[214:217], v[178:181], v[64:67]
	v_mfma_f32_16x16x32_bf16 v[170:173], v[218:221], v[178:181], v[170:173]
	ds_read_b128 v[178:181], v29
	v_mfma_f32_16x16x32_bf16 v[80:83], v[214:217], v[222:225], v[80:83]
	v_mfma_f32_16x16x32_bf16 v[32:35], v[218:221], v[222:225], v[32:35]
	ds_read_b128 v[222:225], v30
	s_waitcnt lgkmcnt(3)
	v_mfma_f32_16x16x32_bf16 v[88:91], v[158:161], v[226:229], v[88:91]
	v_mfma_f32_16x16x32_bf16 v[92:95], v[162:165], v[226:229], v[92:95]
	v_mfma_f32_16x16x32_bf16 v[96:99], v[214:217], v[226:229], v[96:99]
	v_mfma_f32_16x16x32_bf16 v[36:39], v[218:221], v[226:229], v[36:39]
	ds_read_b128 v[226:229], v31
	s_waitcnt lgkmcnt(3)
	v_mfma_f32_16x16x32_bf16 v[104:107], v[158:161], v[166:169], v[104:107]
	v_mfma_f32_16x16x32_bf16 v[108:111], v[162:165], v[166:169], v[108:111]
	v_mfma_f32_16x16x32_bf16 v[112:115], v[214:217], v[166:169], v[112:115]
	v_mfma_f32_16x16x32_bf16 v[52:55], v[218:221], v[166:169], v[52:55]
	s_waitcnt lgkmcnt(2)
	v_mfma_f32_16x16x32_bf16 v[116:119], v[158:161], v[178:181], v[116:119]
	v_mfma_f32_16x16x32_bf16 v[120:123], v[162:165], v[178:181], v[120:123]
	v_mfma_f32_16x16x32_bf16 v[124:127], v[214:217], v[178:181], v[124:127]
	v_mfma_f32_16x16x32_bf16 v[68:71], v[218:221], v[178:181], v[68:71]
	s_waitcnt lgkmcnt(1)
	v_mfma_f32_16x16x32_bf16 v[128:131], v[158:161], v[222:225], v[128:131]
	v_mfma_f32_16x16x32_bf16 v[132:135], v[162:165], v[222:225], v[132:135]
	v_mfma_f32_16x16x32_bf16 v[136:139], v[214:217], v[222:225], v[136:139]
	v_mfma_f32_16x16x32_bf16 v[84:87], v[218:221], v[222:225], v[84:87]
	s_waitcnt lgkmcnt(0)
	v_mfma_f32_16x16x32_bf16 v[100:103], v[158:161], v[226:229], v[100:103]
	v_mfma_f32_16x16x32_bf16 v[140:143], v[162:165], v[226:229], v[140:143]
	v_mfma_f32_16x16x32_bf16 v[150:153], v[214:217], v[226:229], v[150:153]
	v_mfma_f32_16x16x32_bf16 v[154:157], v[218:221], v[226:229], v[154:157]
	s_add_u32 s64, s0, 0x1980
	s_addc_u32 s65, s1, 0
	s_add_u32 s68, s14, 0x1980
	s_waitcnt vmcnt(0)
	s_barrier
	s_addc_u32 s69, s15, 0
	ds_read_b128 v[158:161], v7 offset:32768
	ds_read_b128 v[162:165], v6
	ds_read_b128 v[166:169], v7 offset:34816
	ds_read_b128 v[178:181], v6 offset:2048
	ds_read_b128 v[214:217], v7 offset:36864
	ds_read_b128 v[218:221], v7 offset:38912
	ds_read_b128 v[222:225], v6 offset:4096
	ds_read_b128 v[226:229], v6 offset:6144
	s_waitcnt lgkmcnt(6)
	v_mfma_f32_16x16x32_bf16 v[40:43], v[158:161], v[162:165], v[40:43]
	s_waitcnt lgkmcnt(5)
	v_mfma_f32_16x16x32_bf16 v[44:47], v[166:169], v[162:165], v[44:47]
	s_waitcnt lgkmcnt(4)
	v_mfma_f32_16x16x32_bf16 v[56:59], v[158:161], v[178:181], v[56:59]
	s_mov_b32 m0, s52
	v_mfma_f32_16x16x32_bf16 v[60:63], v[166:169], v[178:181], v[60:63]
	global_load_lds_dwordx4 v0, s[64:65]
	s_waitcnt lgkmcnt(3)
	v_mfma_f32_16x16x32_bf16 v[48:51], v[214:217], v[162:165], v[48:51]
	v_mfma_f32_16x16x32_bf16 v[64:67], v[214:217], v[178:181], v[64:67]
	s_waitcnt lgkmcnt(2)
	v_mfma_f32_16x16x32_bf16 v[174:177], v[218:221], v[162:165], v[174:177]
	ds_read_b128 v[162:165], v6 offset:8192
	v_mfma_f32_16x16x32_bf16 v[170:173], v[218:221], v[178:181], v[170:173]
	ds_read_b128 v[178:181], v6 offset:10240
	s_waitcnt lgkmcnt(3)
	s_mov_b32 m0, s51
	v_mfma_f32_16x16x32_bf16 v[72:75], v[158:161], v[222:225], v[72:75]
	global_load_lds_dwordx4 v0, s[68:69]
	v_mfma_f32_16x16x32_bf16 v[76:79], v[166:169], v[222:225], v[76:79]
	v_mfma_f32_16x16x32_bf16 v[80:83], v[214:217], v[222:225], v[80:83]
	v_mfma_f32_16x16x32_bf16 v[32:35], v[218:221], v[222:225], v[32:35]
	ds_read_b128 v[222:225], v6 offset:12288
	s_waitcnt lgkmcnt(3)
	v_mfma_f32_16x16x32_bf16 v[88:91], v[158:161], v[226:229], v[88:91]
	s_mov_b32 m0, s53
	v_mfma_f32_16x16x32_bf16 v[92:95], v[166:169], v[226:229], v[92:95]
	global_load_lds_dwordx4 v2, s[64:65]
	v_mfma_f32_16x16x32_bf16 v[96:99], v[214:217], v[226:229], v[96:99]
	v_mfma_f32_16x16x32_bf16 v[36:39], v[218:221], v[226:229], v[36:39]
	ds_read_b128 v[226:229], v6 offset:14336
	s_waitcnt lgkmcnt(3)
	v_mfma_f32_16x16x32_bf16 v[104:107], v[158:161], v[162:165], v[104:107]
	s_waitcnt lgkmcnt(2)
	v_mfma_f32_16x16x32_bf16 v[116:119], v[158:161], v[178:181], v[116:119]
	s_waitcnt lgkmcnt(1)
	s_mov_b32 m0, s54
	v_mfma_f32_16x16x32_bf16 v[128:131], v[158:161], v[222:225], v[128:131]
	global_load_lds_dwordx4 v2, s[68:69]
	s_waitcnt lgkmcnt(0)
	v_mfma_f32_16x16x32_bf16 v[100:103], v[158:161], v[226:229], v[100:103]
	ds_read_b128 v[158:161], v7 offset:33792
	v_mfma_f32_16x16x32_bf16 v[108:111], v[166:169], v[162:165], v[108:111]
	v_mfma_f32_16x16x32_bf16 v[120:123], v[166:169], v[178:181], v[120:123]
	v_mfma_f32_16x16x32_bf16 v[132:135], v[166:169], v[222:225], v[132:135]
	s_mov_b32 m0, s55
	v_mfma_f32_16x16x32_bf16 v[140:143], v[166:169], v[226:229], v[140:143]
	global_load_lds_dwordx4 v4, s[64:65]
	ds_read_b128 v[166:169], v6 offset:1024
	v_mfma_f32_16x16x32_bf16 v[112:115], v[214:217], v[162:165], v[112:115]
	v_mfma_f32_16x16x32_bf16 v[52:55], v[218:221], v[162:165], v[52:55]
	ds_read_b128 v[162:165], v7 offset:35840
	v_mfma_f32_16x16x32_bf16 v[124:127], v[214:217], v[178:181], v[124:127]
	v_mfma_f32_16x16x32_bf16 v[68:71], v[218:221], v[178:181], v[68:71]
	ds_read_b128 v[178:181], v6 offset:3072
	s_mov_b32 m0, s58
	v_mfma_f32_16x16x32_bf16 v[136:139], v[214:217], v[222:225], v[136:139]
	global_load_lds_dwordx4 v4, s[68:69]
	v_mfma_f32_16x16x32_bf16 v[84:87], v[218:221], v[222:225], v[84:87]
	ds_read_b128 v[222:225], v6 offset:5120
	v_mfma_f32_16x16x32_bf16 v[150:153], v[214:217], v[226:229], v[150:153]
	ds_read_b128 v[214:217], v7 offset:37888
	v_mfma_f32_16x16x32_bf16 v[154:157], v[218:221], v[226:229], v[154:157]
	ds_read_b128 v[218:221], v7 offset:39936
	ds_read_b128 v[226:229], v6 offset:7168
	s_waitcnt lgkmcnt(6)
	v_mfma_f32_16x16x32_bf16 v[40:43], v[158:161], v[166:169], v[40:43]
	s_waitcnt lgkmcnt(5)
	s_mov_b32 m0, s62
	v_mfma_f32_16x16x32_bf16 v[44:47], v[162:165], v[166:169], v[44:47]
	global_load_lds_dwordx4 v146, s[64:65]
	s_waitcnt lgkmcnt(4)
	v_mfma_f32_16x16x32_bf16 v[56:59], v[158:161], v[178:181], v[56:59]
	v_mfma_f32_16x16x32_bf16 v[60:63], v[162:165], v[178:181], v[60:63]
	s_waitcnt lgkmcnt(3)
	v_mfma_f32_16x16x32_bf16 v[72:75], v[158:161], v[222:225], v[72:75]
	v_mfma_f32_16x16x32_bf16 v[76:79], v[162:165], v[222:225], v[76:79]
	s_waitcnt lgkmcnt(2)
	s_mov_b32 m0, s63
	v_mfma_f32_16x16x32_bf16 v[48:51], v[214:217], v[166:169], v[48:51]
	global_load_lds_dwordx4 v146, s[68:69]
	s_waitcnt lgkmcnt(1)
	v_mfma_f32_16x16x32_bf16 v[174:177], v[218:221], v[166:169], v[174:177]
	ds_read_b128 v[166:169], v6 offset:9216
	v_mfma_f32_16x16x32_bf16 v[64:67], v[214:217], v[178:181], v[64:67]
	v_mfma_f32_16x16x32_bf16 v[170:173], v[218:221], v[178:181], v[170:173]
	ds_read_b128 v[178:181], v6 offset:11264
	v_mfma_f32_16x16x32_bf16 v[80:83], v[214:217], v[222:225], v[80:83]
	v_mfma_f32_16x16x32_bf16 v[32:35], v[218:221], v[222:225], v[32:35]
	ds_read_b128 v[222:225], v6 offset:13312
	s_waitcnt lgkmcnt(3)
	v_mfma_f32_16x16x32_bf16 v[88:91], v[158:161], v[226:229], v[88:91]
	v_mfma_f32_16x16x32_bf16 v[92:95], v[162:165], v[226:229], v[92:95]
	v_mfma_f32_16x16x32_bf16 v[96:99], v[214:217], v[226:229], v[96:99]
	v_mfma_f32_16x16x32_bf16 v[36:39], v[218:221], v[226:229], v[36:39]
	ds_read_b128 v[226:229], v6 offset:15360
	s_waitcnt lgkmcnt(3)
	v_mfma_f32_16x16x32_bf16 v[104:107], v[158:161], v[166:169], v[104:107]
	v_mfma_f32_16x16x32_bf16 v[108:111], v[162:165], v[166:169], v[108:111]
	v_mfma_f32_16x16x32_bf16 v[112:115], v[214:217], v[166:169], v[112:115]
	v_mfma_f32_16x16x32_bf16 v[52:55], v[218:221], v[166:169], v[52:55]
	s_waitcnt lgkmcnt(2)
	v_mfma_f32_16x16x32_bf16 v[116:119], v[158:161], v[178:181], v[116:119]
	v_mfma_f32_16x16x32_bf16 v[120:123], v[162:165], v[178:181], v[120:123]
	v_mfma_f32_16x16x32_bf16 v[124:127], v[214:217], v[178:181], v[124:127]
	v_mfma_f32_16x16x32_bf16 v[68:71], v[218:221], v[178:181], v[68:71]
	s_waitcnt lgkmcnt(1)
	v_mfma_f32_16x16x32_bf16 v[128:131], v[158:161], v[222:225], v[128:131]
	v_mfma_f32_16x16x32_bf16 v[132:135], v[162:165], v[222:225], v[132:135]
	v_mfma_f32_16x16x32_bf16 v[136:139], v[214:217], v[222:225], v[136:139]
	v_mfma_f32_16x16x32_bf16 v[84:87], v[218:221], v[222:225], v[84:87]
	s_waitcnt lgkmcnt(0)
	v_mfma_f32_16x16x32_bf16 v[100:103], v[158:161], v[226:229], v[100:103]
	v_mfma_f32_16x16x32_bf16 v[140:143], v[162:165], v[226:229], v[140:143]
	v_mfma_f32_16x16x32_bf16 v[150:153], v[214:217], v[226:229], v[150:153]
	v_mfma_f32_16x16x32_bf16 v[154:157], v[218:221], v[226:229], v[154:157]
	s_add_u32 s64, s0, 0x1a00
	s_addc_u32 s65, s1, 0
	s_add_u32 s68, s14, 0x1a00
	s_waitcnt vmcnt(0)
	s_barrier
	s_addc_u32 s69, s15, 0
	ds_read_b128 v[158:161], v8
	ds_read_b128 v[162:165], v12
	ds_read_b128 v[166:169], v9
	ds_read_b128 v[178:181], v13
	ds_read_b128 v[214:217], v11
	ds_read_b128 v[218:221], v10
	ds_read_b128 v[222:225], v14
	ds_read_b128 v[226:229], v15
	s_waitcnt lgkmcnt(6)
	v_mfma_f32_16x16x32_bf16 v[40:43], v[158:161], v[162:165], v[40:43]
	s_waitcnt lgkmcnt(5)
	v_mfma_f32_16x16x32_bf16 v[44:47], v[166:169], v[162:165], v[44:47]
	s_waitcnt lgkmcnt(4)
	v_mfma_f32_16x16x32_bf16 v[56:59], v[158:161], v[178:181], v[56:59]
	s_mov_b32 m0, s42
	v_mfma_f32_16x16x32_bf16 v[60:63], v[166:169], v[178:181], v[60:63]
	global_load_lds_dwordx4 v0, s[64:65]
	s_waitcnt lgkmcnt(3)
	v_mfma_f32_16x16x32_bf16 v[48:51], v[214:217], v[162:165], v[48:51]
	v_mfma_f32_16x16x32_bf16 v[64:67], v[214:217], v[178:181], v[64:67]
	s_waitcnt lgkmcnt(2)
	v_mfma_f32_16x16x32_bf16 v[174:177], v[218:221], v[162:165], v[174:177]
	ds_read_b128 v[162:165], v16
	v_mfma_f32_16x16x32_bf16 v[170:173], v[218:221], v[178:181], v[170:173]
	ds_read_b128 v[178:181], v17
	s_waitcnt lgkmcnt(3)
	s_mov_b32 m0, s43
	v_mfma_f32_16x16x32_bf16 v[72:75], v[158:161], v[222:225], v[72:75]
	global_load_lds_dwordx4 v0, s[68:69]
	v_mfma_f32_16x16x32_bf16 v[76:79], v[166:169], v[222:225], v[76:79]
	v_mfma_f32_16x16x32_bf16 v[80:83], v[214:217], v[222:225], v[80:83]
	v_mfma_f32_16x16x32_bf16 v[32:35], v[218:221], v[222:225], v[32:35]
	ds_read_b128 v[222:225], v18
	s_waitcnt lgkmcnt(3)
	v_mfma_f32_16x16x32_bf16 v[88:91], v[158:161], v[226:229], v[88:91]
	s_mov_b32 m0, s44
	v_mfma_f32_16x16x32_bf16 v[92:95], v[166:169], v[226:229], v[92:95]
	global_load_lds_dwordx4 v2, s[64:65]
	v_mfma_f32_16x16x32_bf16 v[96:99], v[214:217], v[226:229], v[96:99]
	v_mfma_f32_16x16x32_bf16 v[36:39], v[218:221], v[226:229], v[36:39]
	ds_read_b128 v[226:229], v19
	s_waitcnt lgkmcnt(3)
	v_mfma_f32_16x16x32_bf16 v[104:107], v[158:161], v[162:165], v[104:107]
	s_waitcnt lgkmcnt(2)
	v_mfma_f32_16x16x32_bf16 v[116:119], v[158:161], v[178:181], v[116:119]
	s_waitcnt lgkmcnt(1)
	s_mov_b32 m0, s45
	v_mfma_f32_16x16x32_bf16 v[128:131], v[158:161], v[222:225], v[128:131]
	global_load_lds_dwordx4 v2, s[68:69]
	s_waitcnt lgkmcnt(0)
	v_mfma_f32_16x16x32_bf16 v[100:103], v[158:161], v[226:229], v[100:103]
	ds_read_b128 v[158:161], v20
	v_mfma_f32_16x16x32_bf16 v[108:111], v[166:169], v[162:165], v[108:111]
	v_mfma_f32_16x16x32_bf16 v[120:123], v[166:169], v[178:181], v[120:123]
	v_mfma_f32_16x16x32_bf16 v[132:135], v[166:169], v[222:225], v[132:135]
	s_mov_b32 m0, s46
	v_mfma_f32_16x16x32_bf16 v[140:143], v[166:169], v[226:229], v[140:143]
	global_load_lds_dwordx4 v4, s[64:65]
	ds_read_b128 v[166:169], v24
	v_mfma_f32_16x16x32_bf16 v[112:115], v[214:217], v[162:165], v[112:115]
	v_mfma_f32_16x16x32_bf16 v[52:55], v[218:221], v[162:165], v[52:55]
	ds_read_b128 v[162:165], v21
	v_mfma_f32_16x16x32_bf16 v[124:127], v[214:217], v[178:181], v[124:127]
	v_mfma_f32_16x16x32_bf16 v[68:71], v[218:221], v[178:181], v[68:71]
	ds_read_b128 v[178:181], v25
	s_mov_b32 m0, s47
	v_mfma_f32_16x16x32_bf16 v[136:139], v[214:217], v[222:225], v[136:139]
	global_load_lds_dwordx4 v4, s[68:69]
	v_mfma_f32_16x16x32_bf16 v[84:87], v[218:221], v[222:225], v[84:87]
	ds_read_b128 v[222:225], v26
	v_mfma_f32_16x16x32_bf16 v[150:153], v[214:217], v[226:229], v[150:153]
	ds_read_b128 v[214:217], v23
	v_mfma_f32_16x16x32_bf16 v[154:157], v[218:221], v[226:229], v[154:157]
	ds_read_b128 v[218:221], v22
	ds_read_b128 v[226:229], v27
	s_waitcnt lgkmcnt(6)
	v_mfma_f32_16x16x32_bf16 v[40:43], v[158:161], v[166:169], v[40:43]
	s_waitcnt lgkmcnt(5)
	s_mov_b32 m0, s49
	v_mfma_f32_16x16x32_bf16 v[44:47], v[162:165], v[166:169], v[44:47]
	global_load_lds_dwordx4 v146, s[64:65]
	s_waitcnt lgkmcnt(4)
	v_mfma_f32_16x16x32_bf16 v[56:59], v[158:161], v[178:181], v[56:59]
	v_mfma_f32_16x16x32_bf16 v[60:63], v[162:165], v[178:181], v[60:63]
	s_waitcnt lgkmcnt(3)
	v_mfma_f32_16x16x32_bf16 v[72:75], v[158:161], v[222:225], v[72:75]
	v_mfma_f32_16x16x32_bf16 v[76:79], v[162:165], v[222:225], v[76:79]
	s_waitcnt lgkmcnt(2)
	s_mov_b32 m0, s50
	v_mfma_f32_16x16x32_bf16 v[48:51], v[214:217], v[166:169], v[48:51]
	global_load_lds_dwordx4 v146, s[68:69]
	s_waitcnt lgkmcnt(1)
	v_mfma_f32_16x16x32_bf16 v[174:177], v[218:221], v[166:169], v[174:177]
	ds_read_b128 v[166:169], v28
	v_mfma_f32_16x16x32_bf16 v[64:67], v[214:217], v[178:181], v[64:67]
	v_mfma_f32_16x16x32_bf16 v[170:173], v[218:221], v[178:181], v[170:173]
	ds_read_b128 v[178:181], v29
	v_mfma_f32_16x16x32_bf16 v[80:83], v[214:217], v[222:225], v[80:83]
	v_mfma_f32_16x16x32_bf16 v[32:35], v[218:221], v[222:225], v[32:35]
	ds_read_b128 v[222:225], v30
	s_waitcnt lgkmcnt(3)
	v_mfma_f32_16x16x32_bf16 v[88:91], v[158:161], v[226:229], v[88:91]
	v_mfma_f32_16x16x32_bf16 v[92:95], v[162:165], v[226:229], v[92:95]
	v_mfma_f32_16x16x32_bf16 v[96:99], v[214:217], v[226:229], v[96:99]
	v_mfma_f32_16x16x32_bf16 v[36:39], v[218:221], v[226:229], v[36:39]
	ds_read_b128 v[226:229], v31
	s_waitcnt lgkmcnt(3)
	v_mfma_f32_16x16x32_bf16 v[104:107], v[158:161], v[166:169], v[104:107]
	v_mfma_f32_16x16x32_bf16 v[108:111], v[162:165], v[166:169], v[108:111]
	v_mfma_f32_16x16x32_bf16 v[112:115], v[214:217], v[166:169], v[112:115]
	v_mfma_f32_16x16x32_bf16 v[52:55], v[218:221], v[166:169], v[52:55]
	s_waitcnt lgkmcnt(2)
	v_mfma_f32_16x16x32_bf16 v[116:119], v[158:161], v[178:181], v[116:119]
	v_mfma_f32_16x16x32_bf16 v[120:123], v[162:165], v[178:181], v[120:123]
	v_mfma_f32_16x16x32_bf16 v[124:127], v[214:217], v[178:181], v[124:127]
	v_mfma_f32_16x16x32_bf16 v[68:71], v[218:221], v[178:181], v[68:71]
	s_waitcnt lgkmcnt(1)
	v_mfma_f32_16x16x32_bf16 v[128:131], v[158:161], v[222:225], v[128:131]
	v_mfma_f32_16x16x32_bf16 v[132:135], v[162:165], v[222:225], v[132:135]
	v_mfma_f32_16x16x32_bf16 v[136:139], v[214:217], v[222:225], v[136:139]
	v_mfma_f32_16x16x32_bf16 v[84:87], v[218:221], v[222:225], v[84:87]
	s_waitcnt lgkmcnt(0)
	v_mfma_f32_16x16x32_bf16 v[100:103], v[158:161], v[226:229], v[100:103]
	v_mfma_f32_16x16x32_bf16 v[140:143], v[162:165], v[226:229], v[140:143]
	v_mfma_f32_16x16x32_bf16 v[150:153], v[214:217], v[226:229], v[150:153]
	v_mfma_f32_16x16x32_bf16 v[154:157], v[218:221], v[226:229], v[154:157]
	s_add_u32 s64, s0, 0x1a80
	s_addc_u32 s65, s1, 0
	s_add_u32 s68, s14, 0x1a80
	s_waitcnt vmcnt(0)
	s_barrier
	s_addc_u32 s69, s15, 0
	ds_read_b128 v[158:161], v7 offset:32768
	ds_read_b128 v[162:165], v6
	ds_read_b128 v[166:169], v7 offset:34816
	ds_read_b128 v[178:181], v6 offset:2048
	ds_read_b128 v[214:217], v7 offset:36864
	ds_read_b128 v[218:221], v7 offset:38912
	ds_read_b128 v[222:225], v6 offset:4096
	ds_read_b128 v[226:229], v6 offset:6144
	s_waitcnt lgkmcnt(6)
	v_mfma_f32_16x16x32_bf16 v[40:43], v[158:161], v[162:165], v[40:43]
	s_waitcnt lgkmcnt(5)
	v_mfma_f32_16x16x32_bf16 v[44:47], v[166:169], v[162:165], v[44:47]
	s_waitcnt lgkmcnt(4)
	v_mfma_f32_16x16x32_bf16 v[56:59], v[158:161], v[178:181], v[56:59]
	s_mov_b32 m0, s52
	v_mfma_f32_16x16x32_bf16 v[60:63], v[166:169], v[178:181], v[60:63]
	global_load_lds_dwordx4 v0, s[64:65]
	s_waitcnt lgkmcnt(3)
	v_mfma_f32_16x16x32_bf16 v[48:51], v[214:217], v[162:165], v[48:51]
	v_mfma_f32_16x16x32_bf16 v[64:67], v[214:217], v[178:181], v[64:67]
	s_waitcnt lgkmcnt(2)
	v_mfma_f32_16x16x32_bf16 v[174:177], v[218:221], v[162:165], v[174:177]
	ds_read_b128 v[162:165], v6 offset:8192
	v_mfma_f32_16x16x32_bf16 v[170:173], v[218:221], v[178:181], v[170:173]
	ds_read_b128 v[178:181], v6 offset:10240
	s_waitcnt lgkmcnt(3)
	s_mov_b32 m0, s51
	v_mfma_f32_16x16x32_bf16 v[72:75], v[158:161], v[222:225], v[72:75]
	global_load_lds_dwordx4 v0, s[68:69]
	v_mfma_f32_16x16x32_bf16 v[76:79], v[166:169], v[222:225], v[76:79]
	v_mfma_f32_16x16x32_bf16 v[80:83], v[214:217], v[222:225], v[80:83]
	v_mfma_f32_16x16x32_bf16 v[32:35], v[218:221], v[222:225], v[32:35]
	ds_read_b128 v[222:225], v6 offset:12288
	s_waitcnt lgkmcnt(3)
	v_mfma_f32_16x16x32_bf16 v[88:91], v[158:161], v[226:229], v[88:91]
	s_mov_b32 m0, s53
	v_mfma_f32_16x16x32_bf16 v[92:95], v[166:169], v[226:229], v[92:95]
	global_load_lds_dwordx4 v2, s[64:65]
	v_mfma_f32_16x16x32_bf16 v[96:99], v[214:217], v[226:229], v[96:99]
	v_mfma_f32_16x16x32_bf16 v[36:39], v[218:221], v[226:229], v[36:39]
	ds_read_b128 v[226:229], v6 offset:14336
	s_waitcnt lgkmcnt(3)
	v_mfma_f32_16x16x32_bf16 v[104:107], v[158:161], v[162:165], v[104:107]
	s_waitcnt lgkmcnt(2)
	v_mfma_f32_16x16x32_bf16 v[116:119], v[158:161], v[178:181], v[116:119]
	s_waitcnt lgkmcnt(1)
	s_mov_b32 m0, s54
	v_mfma_f32_16x16x32_bf16 v[128:131], v[158:161], v[222:225], v[128:131]
	global_load_lds_dwordx4 v2, s[68:69]
	s_waitcnt lgkmcnt(0)
	v_mfma_f32_16x16x32_bf16 v[100:103], v[158:161], v[226:229], v[100:103]
	ds_read_b128 v[158:161], v7 offset:33792
	v_mfma_f32_16x16x32_bf16 v[108:111], v[166:169], v[162:165], v[108:111]
	v_mfma_f32_16x16x32_bf16 v[120:123], v[166:169], v[178:181], v[120:123]
	v_mfma_f32_16x16x32_bf16 v[132:135], v[166:169], v[222:225], v[132:135]
	s_mov_b32 m0, s55
	v_mfma_f32_16x16x32_bf16 v[140:143], v[166:169], v[226:229], v[140:143]
	global_load_lds_dwordx4 v4, s[64:65]
	ds_read_b128 v[166:169], v6 offset:1024
	v_mfma_f32_16x16x32_bf16 v[112:115], v[214:217], v[162:165], v[112:115]
	v_mfma_f32_16x16x32_bf16 v[52:55], v[218:221], v[162:165], v[52:55]
	ds_read_b128 v[162:165], v7 offset:35840
	v_mfma_f32_16x16x32_bf16 v[124:127], v[214:217], v[178:181], v[124:127]
	v_mfma_f32_16x16x32_bf16 v[68:71], v[218:221], v[178:181], v[68:71]
	ds_read_b128 v[178:181], v6 offset:3072
	s_mov_b32 m0, s58
	v_mfma_f32_16x16x32_bf16 v[136:139], v[214:217], v[222:225], v[136:139]
	global_load_lds_dwordx4 v4, s[68:69]
	v_mfma_f32_16x16x32_bf16 v[84:87], v[218:221], v[222:225], v[84:87]
	ds_read_b128 v[222:225], v6 offset:5120
	v_mfma_f32_16x16x32_bf16 v[150:153], v[214:217], v[226:229], v[150:153]
	ds_read_b128 v[214:217], v7 offset:37888
	v_mfma_f32_16x16x32_bf16 v[154:157], v[218:221], v[226:229], v[154:157]
	ds_read_b128 v[218:221], v7 offset:39936
	ds_read_b128 v[226:229], v6 offset:7168
	s_waitcnt lgkmcnt(6)
	v_mfma_f32_16x16x32_bf16 v[40:43], v[158:161], v[166:169], v[40:43]
	s_waitcnt lgkmcnt(5)
	s_mov_b32 m0, s62
	v_mfma_f32_16x16x32_bf16 v[44:47], v[162:165], v[166:169], v[44:47]
	global_load_lds_dwordx4 v146, s[64:65]
	s_waitcnt lgkmcnt(4)
	v_mfma_f32_16x16x32_bf16 v[56:59], v[158:161], v[178:181], v[56:59]
	v_mfma_f32_16x16x32_bf16 v[60:63], v[162:165], v[178:181], v[60:63]
	s_waitcnt lgkmcnt(3)
	v_mfma_f32_16x16x32_bf16 v[72:75], v[158:161], v[222:225], v[72:75]
	v_mfma_f32_16x16x32_bf16 v[76:79], v[162:165], v[222:225], v[76:79]
	s_waitcnt lgkmcnt(2)
	s_mov_b32 m0, s63
	v_mfma_f32_16x16x32_bf16 v[48:51], v[214:217], v[166:169], v[48:51]
	global_load_lds_dwordx4 v146, s[68:69]
	s_waitcnt lgkmcnt(1)
	v_mfma_f32_16x16x32_bf16 v[174:177], v[218:221], v[166:169], v[174:177]
	ds_read_b128 v[166:169], v6 offset:9216
	v_mfma_f32_16x16x32_bf16 v[64:67], v[214:217], v[178:181], v[64:67]
	v_mfma_f32_16x16x32_bf16 v[170:173], v[218:221], v[178:181], v[170:173]
	ds_read_b128 v[178:181], v6 offset:11264
	v_mfma_f32_16x16x32_bf16 v[80:83], v[214:217], v[222:225], v[80:83]
	v_mfma_f32_16x16x32_bf16 v[32:35], v[218:221], v[222:225], v[32:35]
	ds_read_b128 v[222:225], v6 offset:13312
	s_waitcnt lgkmcnt(3)
	v_mfma_f32_16x16x32_bf16 v[88:91], v[158:161], v[226:229], v[88:91]
	v_mfma_f32_16x16x32_bf16 v[92:95], v[162:165], v[226:229], v[92:95]
	v_mfma_f32_16x16x32_bf16 v[96:99], v[214:217], v[226:229], v[96:99]
	v_mfma_f32_16x16x32_bf16 v[36:39], v[218:221], v[226:229], v[36:39]
	ds_read_b128 v[226:229], v6 offset:15360
	s_waitcnt lgkmcnt(3)
	v_mfma_f32_16x16x32_bf16 v[104:107], v[158:161], v[166:169], v[104:107]
	v_mfma_f32_16x16x32_bf16 v[108:111], v[162:165], v[166:169], v[108:111]
	v_mfma_f32_16x16x32_bf16 v[112:115], v[214:217], v[166:169], v[112:115]
	v_mfma_f32_16x16x32_bf16 v[52:55], v[218:221], v[166:169], v[52:55]
	s_waitcnt lgkmcnt(2)
	v_mfma_f32_16x16x32_bf16 v[116:119], v[158:161], v[178:181], v[116:119]
	v_mfma_f32_16x16x32_bf16 v[120:123], v[162:165], v[178:181], v[120:123]
	v_mfma_f32_16x16x32_bf16 v[124:127], v[214:217], v[178:181], v[124:127]
	v_mfma_f32_16x16x32_bf16 v[68:71], v[218:221], v[178:181], v[68:71]
	s_waitcnt lgkmcnt(1)
	v_mfma_f32_16x16x32_bf16 v[128:131], v[158:161], v[222:225], v[128:131]
	v_mfma_f32_16x16x32_bf16 v[132:135], v[162:165], v[222:225], v[132:135]
	v_mfma_f32_16x16x32_bf16 v[136:139], v[214:217], v[222:225], v[136:139]
	v_mfma_f32_16x16x32_bf16 v[84:87], v[218:221], v[222:225], v[84:87]
	s_waitcnt lgkmcnt(0)
	v_mfma_f32_16x16x32_bf16 v[100:103], v[158:161], v[226:229], v[100:103]
	v_mfma_f32_16x16x32_bf16 v[140:143], v[162:165], v[226:229], v[140:143]
	v_mfma_f32_16x16x32_bf16 v[150:153], v[214:217], v[226:229], v[150:153]
	v_mfma_f32_16x16x32_bf16 v[154:157], v[218:221], v[226:229], v[154:157]
	s_add_u32 s64, s0, 0x1b00
	s_addc_u32 s65, s1, 0
	s_add_u32 s68, s14, 0x1b00
	s_waitcnt vmcnt(0)
	s_barrier
	s_addc_u32 s69, s15, 0
	ds_read_b128 v[158:161], v8
	ds_read_b128 v[162:165], v12
	ds_read_b128 v[166:169], v9
	ds_read_b128 v[178:181], v13
	ds_read_b128 v[214:217], v11
	ds_read_b128 v[218:221], v10
	ds_read_b128 v[222:225], v14
	ds_read_b128 v[226:229], v15
	s_waitcnt lgkmcnt(6)
	v_mfma_f32_16x16x32_bf16 v[40:43], v[158:161], v[162:165], v[40:43]
	s_waitcnt lgkmcnt(5)
	v_mfma_f32_16x16x32_bf16 v[44:47], v[166:169], v[162:165], v[44:47]
	s_waitcnt lgkmcnt(4)
	v_mfma_f32_16x16x32_bf16 v[56:59], v[158:161], v[178:181], v[56:59]
	s_mov_b32 m0, s42
	v_mfma_f32_16x16x32_bf16 v[60:63], v[166:169], v[178:181], v[60:63]
	global_load_lds_dwordx4 v0, s[64:65]
	s_waitcnt lgkmcnt(3)
	v_mfma_f32_16x16x32_bf16 v[48:51], v[214:217], v[162:165], v[48:51]
	v_mfma_f32_16x16x32_bf16 v[64:67], v[214:217], v[178:181], v[64:67]
	s_waitcnt lgkmcnt(2)
	v_mfma_f32_16x16x32_bf16 v[174:177], v[218:221], v[162:165], v[174:177]
	ds_read_b128 v[162:165], v16
	v_mfma_f32_16x16x32_bf16 v[170:173], v[218:221], v[178:181], v[170:173]
	ds_read_b128 v[178:181], v17
	s_waitcnt lgkmcnt(3)
	s_mov_b32 m0, s43
	v_mfma_f32_16x16x32_bf16 v[72:75], v[158:161], v[222:225], v[72:75]
	global_load_lds_dwordx4 v0, s[68:69]
	v_mfma_f32_16x16x32_bf16 v[76:79], v[166:169], v[222:225], v[76:79]
	v_mfma_f32_16x16x32_bf16 v[80:83], v[214:217], v[222:225], v[80:83]
	v_mfma_f32_16x16x32_bf16 v[32:35], v[218:221], v[222:225], v[32:35]
	ds_read_b128 v[222:225], v18
	s_waitcnt lgkmcnt(3)
	v_mfma_f32_16x16x32_bf16 v[88:91], v[158:161], v[226:229], v[88:91]
	s_mov_b32 m0, s44
	v_mfma_f32_16x16x32_bf16 v[92:95], v[166:169], v[226:229], v[92:95]
	global_load_lds_dwordx4 v2, s[64:65]
	v_mfma_f32_16x16x32_bf16 v[96:99], v[214:217], v[226:229], v[96:99]
	v_mfma_f32_16x16x32_bf16 v[36:39], v[218:221], v[226:229], v[36:39]
	ds_read_b128 v[226:229], v19
	s_waitcnt lgkmcnt(3)
	v_mfma_f32_16x16x32_bf16 v[104:107], v[158:161], v[162:165], v[104:107]
	s_waitcnt lgkmcnt(2)
	v_mfma_f32_16x16x32_bf16 v[116:119], v[158:161], v[178:181], v[116:119]
	s_waitcnt lgkmcnt(1)
	s_mov_b32 m0, s45
	v_mfma_f32_16x16x32_bf16 v[128:131], v[158:161], v[222:225], v[128:131]
	global_load_lds_dwordx4 v2, s[68:69]
	s_waitcnt lgkmcnt(0)
	v_mfma_f32_16x16x32_bf16 v[100:103], v[158:161], v[226:229], v[100:103]
	ds_read_b128 v[158:161], v20
	v_mfma_f32_16x16x32_bf16 v[108:111], v[166:169], v[162:165], v[108:111]
	v_mfma_f32_16x16x32_bf16 v[120:123], v[166:169], v[178:181], v[120:123]
	v_mfma_f32_16x16x32_bf16 v[132:135], v[166:169], v[222:225], v[132:135]
	s_mov_b32 m0, s46
	v_mfma_f32_16x16x32_bf16 v[140:143], v[166:169], v[226:229], v[140:143]
	global_load_lds_dwordx4 v4, s[64:65]
	ds_read_b128 v[166:169], v24
	v_mfma_f32_16x16x32_bf16 v[112:115], v[214:217], v[162:165], v[112:115]
	v_mfma_f32_16x16x32_bf16 v[52:55], v[218:221], v[162:165], v[52:55]
	ds_read_b128 v[162:165], v21
	v_mfma_f32_16x16x32_bf16 v[124:127], v[214:217], v[178:181], v[124:127]
	v_mfma_f32_16x16x32_bf16 v[68:71], v[218:221], v[178:181], v[68:71]
	ds_read_b128 v[178:181], v25
	s_mov_b32 m0, s47
	v_mfma_f32_16x16x32_bf16 v[136:139], v[214:217], v[222:225], v[136:139]
	global_load_lds_dwordx4 v4, s[68:69]
	v_mfma_f32_16x16x32_bf16 v[84:87], v[218:221], v[222:225], v[84:87]
	ds_read_b128 v[222:225], v26
	v_mfma_f32_16x16x32_bf16 v[150:153], v[214:217], v[226:229], v[150:153]
	ds_read_b128 v[214:217], v23
	v_mfma_f32_16x16x32_bf16 v[154:157], v[218:221], v[226:229], v[154:157]
	ds_read_b128 v[218:221], v22
	ds_read_b128 v[226:229], v27
	s_waitcnt lgkmcnt(6)
	v_mfma_f32_16x16x32_bf16 v[40:43], v[158:161], v[166:169], v[40:43]
	s_waitcnt lgkmcnt(5)
	s_mov_b32 m0, s49
	v_mfma_f32_16x16x32_bf16 v[44:47], v[162:165], v[166:169], v[44:47]
	global_load_lds_dwordx4 v146, s[64:65]
	s_waitcnt lgkmcnt(4)
	v_mfma_f32_16x16x32_bf16 v[56:59], v[158:161], v[178:181], v[56:59]
	v_mfma_f32_16x16x32_bf16 v[60:63], v[162:165], v[178:181], v[60:63]
	s_waitcnt lgkmcnt(3)
	v_mfma_f32_16x16x32_bf16 v[72:75], v[158:161], v[222:225], v[72:75]
	v_mfma_f32_16x16x32_bf16 v[76:79], v[162:165], v[222:225], v[76:79]
	s_waitcnt lgkmcnt(2)
	s_mov_b32 m0, s50
	v_mfma_f32_16x16x32_bf16 v[48:51], v[214:217], v[166:169], v[48:51]
	global_load_lds_dwordx4 v146, s[68:69]
	s_waitcnt lgkmcnt(1)
	v_mfma_f32_16x16x32_bf16 v[174:177], v[218:221], v[166:169], v[174:177]
	ds_read_b128 v[166:169], v28
	v_mfma_f32_16x16x32_bf16 v[64:67], v[214:217], v[178:181], v[64:67]
	v_mfma_f32_16x16x32_bf16 v[170:173], v[218:221], v[178:181], v[170:173]
	ds_read_b128 v[178:181], v29
	v_mfma_f32_16x16x32_bf16 v[80:83], v[214:217], v[222:225], v[80:83]
	v_mfma_f32_16x16x32_bf16 v[32:35], v[218:221], v[222:225], v[32:35]
	ds_read_b128 v[222:225], v30
	s_waitcnt lgkmcnt(3)
	v_mfma_f32_16x16x32_bf16 v[88:91], v[158:161], v[226:229], v[88:91]
	v_mfma_f32_16x16x32_bf16 v[92:95], v[162:165], v[226:229], v[92:95]
	v_mfma_f32_16x16x32_bf16 v[96:99], v[214:217], v[226:229], v[96:99]
	v_mfma_f32_16x16x32_bf16 v[36:39], v[218:221], v[226:229], v[36:39]
	ds_read_b128 v[226:229], v31
	s_waitcnt lgkmcnt(3)
	v_mfma_f32_16x16x32_bf16 v[104:107], v[158:161], v[166:169], v[104:107]
	v_mfma_f32_16x16x32_bf16 v[108:111], v[162:165], v[166:169], v[108:111]
	v_mfma_f32_16x16x32_bf16 v[112:115], v[214:217], v[166:169], v[112:115]
	v_mfma_f32_16x16x32_bf16 v[52:55], v[218:221], v[166:169], v[52:55]
	s_waitcnt lgkmcnt(2)
	v_mfma_f32_16x16x32_bf16 v[116:119], v[158:161], v[178:181], v[116:119]
	v_mfma_f32_16x16x32_bf16 v[120:123], v[162:165], v[178:181], v[120:123]
	v_mfma_f32_16x16x32_bf16 v[124:127], v[214:217], v[178:181], v[124:127]
	v_mfma_f32_16x16x32_bf16 v[68:71], v[218:221], v[178:181], v[68:71]
	s_waitcnt lgkmcnt(1)
	v_mfma_f32_16x16x32_bf16 v[128:131], v[158:161], v[222:225], v[128:131]
	v_mfma_f32_16x16x32_bf16 v[132:135], v[162:165], v[222:225], v[132:135]
	v_mfma_f32_16x16x32_bf16 v[136:139], v[214:217], v[222:225], v[136:139]
	v_mfma_f32_16x16x32_bf16 v[84:87], v[218:221], v[222:225], v[84:87]
	s_waitcnt lgkmcnt(0)
	v_mfma_f32_16x16x32_bf16 v[100:103], v[158:161], v[226:229], v[100:103]
	v_mfma_f32_16x16x32_bf16 v[140:143], v[162:165], v[226:229], v[140:143]
	v_mfma_f32_16x16x32_bf16 v[150:153], v[214:217], v[226:229], v[150:153]
	v_mfma_f32_16x16x32_bf16 v[154:157], v[218:221], v[226:229], v[154:157]
	s_add_u32 s64, s0, 0x1b80
	s_addc_u32 s65, s1, 0
	s_add_u32 s68, s14, 0x1b80
	s_waitcnt vmcnt(0)
	s_barrier
	s_addc_u32 s69, s15, 0
	ds_read_b128 v[158:161], v7 offset:32768
	ds_read_b128 v[162:165], v6
	ds_read_b128 v[166:169], v7 offset:34816
	ds_read_b128 v[178:181], v6 offset:2048
	ds_read_b128 v[214:217], v7 offset:36864
	ds_read_b128 v[218:221], v7 offset:38912
	ds_read_b128 v[222:225], v6 offset:4096
	ds_read_b128 v[226:229], v6 offset:6144
	s_waitcnt lgkmcnt(6)
	v_mfma_f32_16x16x32_bf16 v[40:43], v[158:161], v[162:165], v[40:43]
	s_waitcnt lgkmcnt(5)
	v_mfma_f32_16x16x32_bf16 v[44:47], v[166:169], v[162:165], v[44:47]
	s_waitcnt lgkmcnt(4)
	v_mfma_f32_16x16x32_bf16 v[56:59], v[158:161], v[178:181], v[56:59]
	s_mov_b32 m0, s52
	v_mfma_f32_16x16x32_bf16 v[60:63], v[166:169], v[178:181], v[60:63]
	global_load_lds_dwordx4 v0, s[64:65]
	s_waitcnt lgkmcnt(3)
	v_mfma_f32_16x16x32_bf16 v[48:51], v[214:217], v[162:165], v[48:51]
	v_mfma_f32_16x16x32_bf16 v[64:67], v[214:217], v[178:181], v[64:67]
	s_waitcnt lgkmcnt(2)
	v_mfma_f32_16x16x32_bf16 v[174:177], v[218:221], v[162:165], v[174:177]
	ds_read_b128 v[162:165], v6 offset:8192
	v_mfma_f32_16x16x32_bf16 v[170:173], v[218:221], v[178:181], v[170:173]
	ds_read_b128 v[178:181], v6 offset:10240
	s_waitcnt lgkmcnt(3)
	s_mov_b32 m0, s51
	v_mfma_f32_16x16x32_bf16 v[72:75], v[158:161], v[222:225], v[72:75]
	global_load_lds_dwordx4 v0, s[68:69]
	v_mfma_f32_16x16x32_bf16 v[76:79], v[166:169], v[222:225], v[76:79]
	v_mfma_f32_16x16x32_bf16 v[80:83], v[214:217], v[222:225], v[80:83]
	v_mfma_f32_16x16x32_bf16 v[32:35], v[218:221], v[222:225], v[32:35]
	ds_read_b128 v[222:225], v6 offset:12288
	s_waitcnt lgkmcnt(3)
	v_mfma_f32_16x16x32_bf16 v[88:91], v[158:161], v[226:229], v[88:91]
	s_mov_b32 m0, s53
	v_mfma_f32_16x16x32_bf16 v[92:95], v[166:169], v[226:229], v[92:95]
	global_load_lds_dwordx4 v2, s[64:65]
	v_mfma_f32_16x16x32_bf16 v[96:99], v[214:217], v[226:229], v[96:99]
	v_mfma_f32_16x16x32_bf16 v[36:39], v[218:221], v[226:229], v[36:39]
	ds_read_b128 v[226:229], v6 offset:14336
	s_waitcnt lgkmcnt(3)
	v_mfma_f32_16x16x32_bf16 v[104:107], v[158:161], v[162:165], v[104:107]
	s_waitcnt lgkmcnt(2)
	v_mfma_f32_16x16x32_bf16 v[116:119], v[158:161], v[178:181], v[116:119]
	s_waitcnt lgkmcnt(1)
	s_mov_b32 m0, s54
	v_mfma_f32_16x16x32_bf16 v[128:131], v[158:161], v[222:225], v[128:131]
	global_load_lds_dwordx4 v2, s[68:69]
	s_waitcnt lgkmcnt(0)
	v_mfma_f32_16x16x32_bf16 v[100:103], v[158:161], v[226:229], v[100:103]
	ds_read_b128 v[158:161], v7 offset:33792
	v_mfma_f32_16x16x32_bf16 v[108:111], v[166:169], v[162:165], v[108:111]
	v_mfma_f32_16x16x32_bf16 v[120:123], v[166:169], v[178:181], v[120:123]
	v_mfma_f32_16x16x32_bf16 v[132:135], v[166:169], v[222:225], v[132:135]
	s_mov_b32 m0, s55
	v_mfma_f32_16x16x32_bf16 v[140:143], v[166:169], v[226:229], v[140:143]
	global_load_lds_dwordx4 v4, s[64:65]
	ds_read_b128 v[166:169], v6 offset:1024
	v_mfma_f32_16x16x32_bf16 v[112:115], v[214:217], v[162:165], v[112:115]
	v_mfma_f32_16x16x32_bf16 v[52:55], v[218:221], v[162:165], v[52:55]
	ds_read_b128 v[162:165], v7 offset:35840
	v_mfma_f32_16x16x32_bf16 v[124:127], v[214:217], v[178:181], v[124:127]
	v_mfma_f32_16x16x32_bf16 v[68:71], v[218:221], v[178:181], v[68:71]
	ds_read_b128 v[178:181], v6 offset:3072
	s_mov_b32 m0, s58
	v_mfma_f32_16x16x32_bf16 v[136:139], v[214:217], v[222:225], v[136:139]
	global_load_lds_dwordx4 v4, s[68:69]
	v_mfma_f32_16x16x32_bf16 v[84:87], v[218:221], v[222:225], v[84:87]
	ds_read_b128 v[222:225], v6 offset:5120
	v_mfma_f32_16x16x32_bf16 v[150:153], v[214:217], v[226:229], v[150:153]
	ds_read_b128 v[214:217], v7 offset:37888
	v_mfma_f32_16x16x32_bf16 v[154:157], v[218:221], v[226:229], v[154:157]
	ds_read_b128 v[218:221], v7 offset:39936
	ds_read_b128 v[226:229], v6 offset:7168
	s_waitcnt lgkmcnt(6)
	v_mfma_f32_16x16x32_bf16 v[40:43], v[158:161], v[166:169], v[40:43]
	s_waitcnt lgkmcnt(5)
	s_mov_b32 m0, s62
	v_mfma_f32_16x16x32_bf16 v[44:47], v[162:165], v[166:169], v[44:47]
	global_load_lds_dwordx4 v146, s[64:65]
	s_waitcnt lgkmcnt(4)
	v_mfma_f32_16x16x32_bf16 v[56:59], v[158:161], v[178:181], v[56:59]
	v_mfma_f32_16x16x32_bf16 v[60:63], v[162:165], v[178:181], v[60:63]
	s_waitcnt lgkmcnt(3)
	v_mfma_f32_16x16x32_bf16 v[72:75], v[158:161], v[222:225], v[72:75]
	v_mfma_f32_16x16x32_bf16 v[76:79], v[162:165], v[222:225], v[76:79]
	s_waitcnt lgkmcnt(2)
	s_mov_b32 m0, s63
	v_mfma_f32_16x16x32_bf16 v[48:51], v[214:217], v[166:169], v[48:51]
	global_load_lds_dwordx4 v146, s[68:69]
	s_waitcnt lgkmcnt(1)
	v_mfma_f32_16x16x32_bf16 v[174:177], v[218:221], v[166:169], v[174:177]
	ds_read_b128 v[166:169], v6 offset:9216
	v_mfma_f32_16x16x32_bf16 v[64:67], v[214:217], v[178:181], v[64:67]
	v_mfma_f32_16x16x32_bf16 v[170:173], v[218:221], v[178:181], v[170:173]
	ds_read_b128 v[178:181], v6 offset:11264
	v_mfma_f32_16x16x32_bf16 v[80:83], v[214:217], v[222:225], v[80:83]
	v_mfma_f32_16x16x32_bf16 v[32:35], v[218:221], v[222:225], v[32:35]
	ds_read_b128 v[222:225], v6 offset:13312
	s_waitcnt lgkmcnt(3)
	v_mfma_f32_16x16x32_bf16 v[88:91], v[158:161], v[226:229], v[88:91]
	v_mfma_f32_16x16x32_bf16 v[92:95], v[162:165], v[226:229], v[92:95]
	v_mfma_f32_16x16x32_bf16 v[96:99], v[214:217], v[226:229], v[96:99]
	v_mfma_f32_16x16x32_bf16 v[36:39], v[218:221], v[226:229], v[36:39]
	ds_read_b128 v[226:229], v6 offset:15360
	s_waitcnt lgkmcnt(3)
	v_mfma_f32_16x16x32_bf16 v[104:107], v[158:161], v[166:169], v[104:107]
	v_mfma_f32_16x16x32_bf16 v[108:111], v[162:165], v[166:169], v[108:111]
	v_mfma_f32_16x16x32_bf16 v[112:115], v[214:217], v[166:169], v[112:115]
	v_mfma_f32_16x16x32_bf16 v[52:55], v[218:221], v[166:169], v[52:55]
	s_waitcnt lgkmcnt(2)
	v_mfma_f32_16x16x32_bf16 v[116:119], v[158:161], v[178:181], v[116:119]
	v_mfma_f32_16x16x32_bf16 v[120:123], v[162:165], v[178:181], v[120:123]
	v_mfma_f32_16x16x32_bf16 v[124:127], v[214:217], v[178:181], v[124:127]
	v_mfma_f32_16x16x32_bf16 v[68:71], v[218:221], v[178:181], v[68:71]
	s_waitcnt lgkmcnt(1)
	v_mfma_f32_16x16x32_bf16 v[128:131], v[158:161], v[222:225], v[128:131]
	v_mfma_f32_16x16x32_bf16 v[132:135], v[162:165], v[222:225], v[132:135]
	v_mfma_f32_16x16x32_bf16 v[136:139], v[214:217], v[222:225], v[136:139]
	v_mfma_f32_16x16x32_bf16 v[84:87], v[218:221], v[222:225], v[84:87]
	s_waitcnt lgkmcnt(0)
	v_mfma_f32_16x16x32_bf16 v[100:103], v[158:161], v[226:229], v[100:103]
	v_mfma_f32_16x16x32_bf16 v[140:143], v[162:165], v[226:229], v[140:143]
	v_mfma_f32_16x16x32_bf16 v[150:153], v[214:217], v[226:229], v[150:153]
	v_mfma_f32_16x16x32_bf16 v[154:157], v[218:221], v[226:229], v[154:157]
	s_add_u32 s64, s0, 0x1c00
	s_addc_u32 s65, s1, 0
	s_add_u32 s68, s14, 0x1c00
	s_waitcnt vmcnt(0)
	s_barrier
	s_addc_u32 s69, s15, 0
	ds_read_b128 v[158:161], v8
	ds_read_b128 v[162:165], v12
	ds_read_b128 v[166:169], v9
	ds_read_b128 v[178:181], v13
	ds_read_b128 v[214:217], v11
	ds_read_b128 v[218:221], v10
	ds_read_b128 v[222:225], v14
	ds_read_b128 v[226:229], v15
	s_waitcnt lgkmcnt(6)
	v_mfma_f32_16x16x32_bf16 v[40:43], v[158:161], v[162:165], v[40:43]
	s_waitcnt lgkmcnt(5)
	v_mfma_f32_16x16x32_bf16 v[44:47], v[166:169], v[162:165], v[44:47]
	s_waitcnt lgkmcnt(4)
	v_mfma_f32_16x16x32_bf16 v[56:59], v[158:161], v[178:181], v[56:59]
	s_mov_b32 m0, s42
	v_mfma_f32_16x16x32_bf16 v[60:63], v[166:169], v[178:181], v[60:63]
	global_load_lds_dwordx4 v0, s[64:65]
	s_waitcnt lgkmcnt(3)
	v_mfma_f32_16x16x32_bf16 v[48:51], v[214:217], v[162:165], v[48:51]
	v_mfma_f32_16x16x32_bf16 v[64:67], v[214:217], v[178:181], v[64:67]
	s_waitcnt lgkmcnt(2)
	v_mfma_f32_16x16x32_bf16 v[174:177], v[218:221], v[162:165], v[174:177]
	ds_read_b128 v[162:165], v16
	v_mfma_f32_16x16x32_bf16 v[170:173], v[218:221], v[178:181], v[170:173]
	ds_read_b128 v[178:181], v17
	s_waitcnt lgkmcnt(3)
	s_mov_b32 m0, s43
	v_mfma_f32_16x16x32_bf16 v[72:75], v[158:161], v[222:225], v[72:75]
	global_load_lds_dwordx4 v0, s[68:69]
	v_mfma_f32_16x16x32_bf16 v[76:79], v[166:169], v[222:225], v[76:79]
	v_mfma_f32_16x16x32_bf16 v[80:83], v[214:217], v[222:225], v[80:83]
	v_mfma_f32_16x16x32_bf16 v[32:35], v[218:221], v[222:225], v[32:35]
	ds_read_b128 v[222:225], v18
	s_waitcnt lgkmcnt(3)
	v_mfma_f32_16x16x32_bf16 v[88:91], v[158:161], v[226:229], v[88:91]
	s_mov_b32 m0, s44
	v_mfma_f32_16x16x32_bf16 v[92:95], v[166:169], v[226:229], v[92:95]
	global_load_lds_dwordx4 v2, s[64:65]
	v_mfma_f32_16x16x32_bf16 v[96:99], v[214:217], v[226:229], v[96:99]
	v_mfma_f32_16x16x32_bf16 v[36:39], v[218:221], v[226:229], v[36:39]
	ds_read_b128 v[226:229], v19
	s_waitcnt lgkmcnt(3)
	v_mfma_f32_16x16x32_bf16 v[104:107], v[158:161], v[162:165], v[104:107]
	s_waitcnt lgkmcnt(2)
	v_mfma_f32_16x16x32_bf16 v[116:119], v[158:161], v[178:181], v[116:119]
	s_waitcnt lgkmcnt(1)
	s_mov_b32 m0, s45
	v_mfma_f32_16x16x32_bf16 v[128:131], v[158:161], v[222:225], v[128:131]
	global_load_lds_dwordx4 v2, s[68:69]
	s_waitcnt lgkmcnt(0)
	v_mfma_f32_16x16x32_bf16 v[100:103], v[158:161], v[226:229], v[100:103]
	ds_read_b128 v[158:161], v20
	v_mfma_f32_16x16x32_bf16 v[108:111], v[166:169], v[162:165], v[108:111]
	v_mfma_f32_16x16x32_bf16 v[120:123], v[166:169], v[178:181], v[120:123]
	v_mfma_f32_16x16x32_bf16 v[132:135], v[166:169], v[222:225], v[132:135]
	s_mov_b32 m0, s46
	v_mfma_f32_16x16x32_bf16 v[140:143], v[166:169], v[226:229], v[140:143]
	global_load_lds_dwordx4 v4, s[64:65]
	ds_read_b128 v[166:169], v24
	v_mfma_f32_16x16x32_bf16 v[112:115], v[214:217], v[162:165], v[112:115]
	v_mfma_f32_16x16x32_bf16 v[52:55], v[218:221], v[162:165], v[52:55]
	ds_read_b128 v[162:165], v21
	v_mfma_f32_16x16x32_bf16 v[124:127], v[214:217], v[178:181], v[124:127]
	v_mfma_f32_16x16x32_bf16 v[68:71], v[218:221], v[178:181], v[68:71]
	ds_read_b128 v[178:181], v25
	s_mov_b32 m0, s47
	v_mfma_f32_16x16x32_bf16 v[136:139], v[214:217], v[222:225], v[136:139]
	global_load_lds_dwordx4 v4, s[68:69]
	v_mfma_f32_16x16x32_bf16 v[84:87], v[218:221], v[222:225], v[84:87]
	ds_read_b128 v[222:225], v26
	v_mfma_f32_16x16x32_bf16 v[150:153], v[214:217], v[226:229], v[150:153]
	ds_read_b128 v[214:217], v23
	v_mfma_f32_16x16x32_bf16 v[154:157], v[218:221], v[226:229], v[154:157]
	ds_read_b128 v[218:221], v22
	ds_read_b128 v[226:229], v27
	s_waitcnt lgkmcnt(6)
	v_mfma_f32_16x16x32_bf16 v[40:43], v[158:161], v[166:169], v[40:43]
	s_waitcnt lgkmcnt(5)
	s_mov_b32 m0, s49
	v_mfma_f32_16x16x32_bf16 v[44:47], v[162:165], v[166:169], v[44:47]
	global_load_lds_dwordx4 v146, s[64:65]
	s_waitcnt lgkmcnt(4)
	v_mfma_f32_16x16x32_bf16 v[56:59], v[158:161], v[178:181], v[56:59]
	v_mfma_f32_16x16x32_bf16 v[60:63], v[162:165], v[178:181], v[60:63]
	s_waitcnt lgkmcnt(3)
	v_mfma_f32_16x16x32_bf16 v[72:75], v[158:161], v[222:225], v[72:75]
	v_mfma_f32_16x16x32_bf16 v[76:79], v[162:165], v[222:225], v[76:79]
	s_waitcnt lgkmcnt(2)
	s_mov_b32 m0, s50
	v_mfma_f32_16x16x32_bf16 v[48:51], v[214:217], v[166:169], v[48:51]
	global_load_lds_dwordx4 v146, s[68:69]
	s_waitcnt lgkmcnt(1)
	v_mfma_f32_16x16x32_bf16 v[174:177], v[218:221], v[166:169], v[174:177]
	ds_read_b128 v[166:169], v28
	v_mfma_f32_16x16x32_bf16 v[64:67], v[214:217], v[178:181], v[64:67]
	v_mfma_f32_16x16x32_bf16 v[170:173], v[218:221], v[178:181], v[170:173]
	ds_read_b128 v[178:181], v29
	v_mfma_f32_16x16x32_bf16 v[80:83], v[214:217], v[222:225], v[80:83]
	v_mfma_f32_16x16x32_bf16 v[32:35], v[218:221], v[222:225], v[32:35]
	ds_read_b128 v[222:225], v30
	s_waitcnt lgkmcnt(3)
	v_mfma_f32_16x16x32_bf16 v[88:91], v[158:161], v[226:229], v[88:91]
	v_mfma_f32_16x16x32_bf16 v[92:95], v[162:165], v[226:229], v[92:95]
	v_mfma_f32_16x16x32_bf16 v[96:99], v[214:217], v[226:229], v[96:99]
	v_mfma_f32_16x16x32_bf16 v[36:39], v[218:221], v[226:229], v[36:39]
	ds_read_b128 v[226:229], v31
	s_waitcnt lgkmcnt(3)
	v_mfma_f32_16x16x32_bf16 v[104:107], v[158:161], v[166:169], v[104:107]
	v_mfma_f32_16x16x32_bf16 v[108:111], v[162:165], v[166:169], v[108:111]
	v_mfma_f32_16x16x32_bf16 v[112:115], v[214:217], v[166:169], v[112:115]
	v_mfma_f32_16x16x32_bf16 v[52:55], v[218:221], v[166:169], v[52:55]
	s_waitcnt lgkmcnt(2)
	v_mfma_f32_16x16x32_bf16 v[116:119], v[158:161], v[178:181], v[116:119]
	v_mfma_f32_16x16x32_bf16 v[120:123], v[162:165], v[178:181], v[120:123]
	v_mfma_f32_16x16x32_bf16 v[124:127], v[214:217], v[178:181], v[124:127]
	v_mfma_f32_16x16x32_bf16 v[68:71], v[218:221], v[178:181], v[68:71]
	s_waitcnt lgkmcnt(1)
	v_mfma_f32_16x16x32_bf16 v[128:131], v[158:161], v[222:225], v[128:131]
	v_mfma_f32_16x16x32_bf16 v[132:135], v[162:165], v[222:225], v[132:135]
	v_mfma_f32_16x16x32_bf16 v[136:139], v[214:217], v[222:225], v[136:139]
	v_mfma_f32_16x16x32_bf16 v[84:87], v[218:221], v[222:225], v[84:87]
	s_waitcnt lgkmcnt(0)
	v_mfma_f32_16x16x32_bf16 v[100:103], v[158:161], v[226:229], v[100:103]
	v_mfma_f32_16x16x32_bf16 v[140:143], v[162:165], v[226:229], v[140:143]
	v_mfma_f32_16x16x32_bf16 v[150:153], v[214:217], v[226:229], v[150:153]
	v_mfma_f32_16x16x32_bf16 v[154:157], v[218:221], v[226:229], v[154:157]
	s_add_u32 s64, s0, 0x1c80
	s_addc_u32 s65, s1, 0
	s_add_u32 s68, s14, 0x1c80
	s_waitcnt vmcnt(0)
	s_barrier
	s_addc_u32 s69, s15, 0
	ds_read_b128 v[158:161], v7 offset:32768
	ds_read_b128 v[162:165], v6
	ds_read_b128 v[166:169], v7 offset:34816
	ds_read_b128 v[178:181], v6 offset:2048
	ds_read_b128 v[214:217], v7 offset:36864
	ds_read_b128 v[218:221], v7 offset:38912
	ds_read_b128 v[222:225], v6 offset:4096
	ds_read_b128 v[226:229], v6 offset:6144
	s_waitcnt lgkmcnt(6)
	v_mfma_f32_16x16x32_bf16 v[40:43], v[158:161], v[162:165], v[40:43]
	s_waitcnt lgkmcnt(5)
	v_mfma_f32_16x16x32_bf16 v[44:47], v[166:169], v[162:165], v[44:47]
	s_waitcnt lgkmcnt(4)
	v_mfma_f32_16x16x32_bf16 v[56:59], v[158:161], v[178:181], v[56:59]
	s_mov_b32 m0, s52
	v_mfma_f32_16x16x32_bf16 v[60:63], v[166:169], v[178:181], v[60:63]
	global_load_lds_dwordx4 v0, s[64:65]
	s_waitcnt lgkmcnt(3)
	v_mfma_f32_16x16x32_bf16 v[48:51], v[214:217], v[162:165], v[48:51]
	v_mfma_f32_16x16x32_bf16 v[64:67], v[214:217], v[178:181], v[64:67]
	s_waitcnt lgkmcnt(2)
	v_mfma_f32_16x16x32_bf16 v[174:177], v[218:221], v[162:165], v[174:177]
	ds_read_b128 v[162:165], v6 offset:8192
	v_mfma_f32_16x16x32_bf16 v[170:173], v[218:221], v[178:181], v[170:173]
	ds_read_b128 v[178:181], v6 offset:10240
	s_waitcnt lgkmcnt(3)
	s_mov_b32 m0, s51
	v_mfma_f32_16x16x32_bf16 v[72:75], v[158:161], v[222:225], v[72:75]
	global_load_lds_dwordx4 v0, s[68:69]
	v_mfma_f32_16x16x32_bf16 v[76:79], v[166:169], v[222:225], v[76:79]
	v_mfma_f32_16x16x32_bf16 v[80:83], v[214:217], v[222:225], v[80:83]
	v_mfma_f32_16x16x32_bf16 v[32:35], v[218:221], v[222:225], v[32:35]
	ds_read_b128 v[222:225], v6 offset:12288
	s_waitcnt lgkmcnt(3)
	v_mfma_f32_16x16x32_bf16 v[88:91], v[158:161], v[226:229], v[88:91]
	s_mov_b32 m0, s53
	v_mfma_f32_16x16x32_bf16 v[92:95], v[166:169], v[226:229], v[92:95]
	global_load_lds_dwordx4 v2, s[64:65]
	v_mfma_f32_16x16x32_bf16 v[96:99], v[214:217], v[226:229], v[96:99]
	v_mfma_f32_16x16x32_bf16 v[36:39], v[218:221], v[226:229], v[36:39]
	ds_read_b128 v[226:229], v6 offset:14336
	s_waitcnt lgkmcnt(3)
	v_mfma_f32_16x16x32_bf16 v[104:107], v[158:161], v[162:165], v[104:107]
	s_waitcnt lgkmcnt(2)
	v_mfma_f32_16x16x32_bf16 v[116:119], v[158:161], v[178:181], v[116:119]
	s_waitcnt lgkmcnt(1)
	s_mov_b32 m0, s54
	v_mfma_f32_16x16x32_bf16 v[128:131], v[158:161], v[222:225], v[128:131]
	global_load_lds_dwordx4 v2, s[68:69]
	s_waitcnt lgkmcnt(0)
	v_mfma_f32_16x16x32_bf16 v[100:103], v[158:161], v[226:229], v[100:103]
	ds_read_b128 v[158:161], v7 offset:33792
	v_mfma_f32_16x16x32_bf16 v[108:111], v[166:169], v[162:165], v[108:111]
	v_mfma_f32_16x16x32_bf16 v[120:123], v[166:169], v[178:181], v[120:123]
	v_mfma_f32_16x16x32_bf16 v[132:135], v[166:169], v[222:225], v[132:135]
	s_mov_b32 m0, s55
	v_mfma_f32_16x16x32_bf16 v[140:143], v[166:169], v[226:229], v[140:143]
	global_load_lds_dwordx4 v4, s[64:65]
	ds_read_b128 v[166:169], v6 offset:1024
	v_mfma_f32_16x16x32_bf16 v[112:115], v[214:217], v[162:165], v[112:115]
	v_mfma_f32_16x16x32_bf16 v[52:55], v[218:221], v[162:165], v[52:55]
	ds_read_b128 v[162:165], v7 offset:35840
	v_mfma_f32_16x16x32_bf16 v[124:127], v[214:217], v[178:181], v[124:127]
	v_mfma_f32_16x16x32_bf16 v[68:71], v[218:221], v[178:181], v[68:71]
	ds_read_b128 v[178:181], v6 offset:3072
	s_mov_b32 m0, s58
	v_mfma_f32_16x16x32_bf16 v[136:139], v[214:217], v[222:225], v[136:139]
	global_load_lds_dwordx4 v4, s[68:69]
	v_mfma_f32_16x16x32_bf16 v[84:87], v[218:221], v[222:225], v[84:87]
	ds_read_b128 v[222:225], v6 offset:5120
	v_mfma_f32_16x16x32_bf16 v[150:153], v[214:217], v[226:229], v[150:153]
	ds_read_b128 v[214:217], v7 offset:37888
	v_mfma_f32_16x16x32_bf16 v[154:157], v[218:221], v[226:229], v[154:157]
	ds_read_b128 v[218:221], v7 offset:39936
	ds_read_b128 v[226:229], v6 offset:7168
	s_waitcnt lgkmcnt(6)
	v_mfma_f32_16x16x32_bf16 v[40:43], v[158:161], v[166:169], v[40:43]
	s_waitcnt lgkmcnt(5)
	s_mov_b32 m0, s62
	v_mfma_f32_16x16x32_bf16 v[44:47], v[162:165], v[166:169], v[44:47]
	global_load_lds_dwordx4 v146, s[64:65]
	s_waitcnt lgkmcnt(4)
	v_mfma_f32_16x16x32_bf16 v[56:59], v[158:161], v[178:181], v[56:59]
	v_mfma_f32_16x16x32_bf16 v[60:63], v[162:165], v[178:181], v[60:63]
	s_waitcnt lgkmcnt(3)
	v_mfma_f32_16x16x32_bf16 v[72:75], v[158:161], v[222:225], v[72:75]
	v_mfma_f32_16x16x32_bf16 v[76:79], v[162:165], v[222:225], v[76:79]
	s_waitcnt lgkmcnt(2)
	s_mov_b32 m0, s63
	v_mfma_f32_16x16x32_bf16 v[48:51], v[214:217], v[166:169], v[48:51]
	global_load_lds_dwordx4 v146, s[68:69]
	s_waitcnt lgkmcnt(1)
	v_mfma_f32_16x16x32_bf16 v[174:177], v[218:221], v[166:169], v[174:177]
	ds_read_b128 v[166:169], v6 offset:9216
	v_mfma_f32_16x16x32_bf16 v[64:67], v[214:217], v[178:181], v[64:67]
	v_mfma_f32_16x16x32_bf16 v[170:173], v[218:221], v[178:181], v[170:173]
	ds_read_b128 v[178:181], v6 offset:11264
	v_mfma_f32_16x16x32_bf16 v[80:83], v[214:217], v[222:225], v[80:83]
	v_mfma_f32_16x16x32_bf16 v[32:35], v[218:221], v[222:225], v[32:35]
	ds_read_b128 v[222:225], v6 offset:13312
	s_waitcnt lgkmcnt(3)
	v_mfma_f32_16x16x32_bf16 v[88:91], v[158:161], v[226:229], v[88:91]
	v_mfma_f32_16x16x32_bf16 v[92:95], v[162:165], v[226:229], v[92:95]
	v_mfma_f32_16x16x32_bf16 v[96:99], v[214:217], v[226:229], v[96:99]
	v_mfma_f32_16x16x32_bf16 v[36:39], v[218:221], v[226:229], v[36:39]
	ds_read_b128 v[226:229], v6 offset:15360
	s_waitcnt lgkmcnt(3)
	v_mfma_f32_16x16x32_bf16 v[104:107], v[158:161], v[166:169], v[104:107]
	v_mfma_f32_16x16x32_bf16 v[108:111], v[162:165], v[166:169], v[108:111]
	v_mfma_f32_16x16x32_bf16 v[112:115], v[214:217], v[166:169], v[112:115]
	v_mfma_f32_16x16x32_bf16 v[52:55], v[218:221], v[166:169], v[52:55]
	s_waitcnt lgkmcnt(2)
	v_mfma_f32_16x16x32_bf16 v[116:119], v[158:161], v[178:181], v[116:119]
	v_mfma_f32_16x16x32_bf16 v[120:123], v[162:165], v[178:181], v[120:123]
	v_mfma_f32_16x16x32_bf16 v[124:127], v[214:217], v[178:181], v[124:127]
	v_mfma_f32_16x16x32_bf16 v[68:71], v[218:221], v[178:181], v[68:71]
	s_waitcnt lgkmcnt(1)
	v_mfma_f32_16x16x32_bf16 v[128:131], v[158:161], v[222:225], v[128:131]
	v_mfma_f32_16x16x32_bf16 v[132:135], v[162:165], v[222:225], v[132:135]
	v_mfma_f32_16x16x32_bf16 v[136:139], v[214:217], v[222:225], v[136:139]
	v_mfma_f32_16x16x32_bf16 v[84:87], v[218:221], v[222:225], v[84:87]
	s_waitcnt lgkmcnt(0)
	v_mfma_f32_16x16x32_bf16 v[100:103], v[158:161], v[226:229], v[100:103]
	v_mfma_f32_16x16x32_bf16 v[140:143], v[162:165], v[226:229], v[140:143]
	v_mfma_f32_16x16x32_bf16 v[150:153], v[214:217], v[226:229], v[150:153]
	v_mfma_f32_16x16x32_bf16 v[154:157], v[218:221], v[226:229], v[154:157]
	s_add_u32 s64, s0, 0x1d00
	s_addc_u32 s65, s1, 0
	s_add_u32 s68, s14, 0x1d00
	s_waitcnt vmcnt(0)
	s_barrier
	s_addc_u32 s69, s15, 0
	ds_read_b128 v[158:161], v8
	ds_read_b128 v[162:165], v12
	ds_read_b128 v[166:169], v9
	ds_read_b128 v[178:181], v13
	ds_read_b128 v[214:217], v11
	ds_read_b128 v[218:221], v10
	ds_read_b128 v[222:225], v14
	ds_read_b128 v[226:229], v15
	s_waitcnt lgkmcnt(6)
	v_mfma_f32_16x16x32_bf16 v[40:43], v[158:161], v[162:165], v[40:43]
	s_waitcnt lgkmcnt(5)
	v_mfma_f32_16x16x32_bf16 v[44:47], v[166:169], v[162:165], v[44:47]
	s_waitcnt lgkmcnt(4)
	v_mfma_f32_16x16x32_bf16 v[56:59], v[158:161], v[178:181], v[56:59]
	s_mov_b32 m0, s42
	v_mfma_f32_16x16x32_bf16 v[60:63], v[166:169], v[178:181], v[60:63]
	global_load_lds_dwordx4 v0, s[64:65]
	s_waitcnt lgkmcnt(3)
	v_mfma_f32_16x16x32_bf16 v[48:51], v[214:217], v[162:165], v[48:51]
	v_mfma_f32_16x16x32_bf16 v[64:67], v[214:217], v[178:181], v[64:67]
	s_waitcnt lgkmcnt(2)
	v_mfma_f32_16x16x32_bf16 v[174:177], v[218:221], v[162:165], v[174:177]
	ds_read_b128 v[162:165], v16
	v_mfma_f32_16x16x32_bf16 v[170:173], v[218:221], v[178:181], v[170:173]
	ds_read_b128 v[178:181], v17
	s_waitcnt lgkmcnt(3)
	s_mov_b32 m0, s43
	v_mfma_f32_16x16x32_bf16 v[72:75], v[158:161], v[222:225], v[72:75]
	global_load_lds_dwordx4 v0, s[68:69]
	v_mfma_f32_16x16x32_bf16 v[76:79], v[166:169], v[222:225], v[76:79]
	v_mfma_f32_16x16x32_bf16 v[80:83], v[214:217], v[222:225], v[80:83]
	v_mfma_f32_16x16x32_bf16 v[32:35], v[218:221], v[222:225], v[32:35]
	ds_read_b128 v[222:225], v18
	s_waitcnt lgkmcnt(3)
	v_mfma_f32_16x16x32_bf16 v[88:91], v[158:161], v[226:229], v[88:91]
	s_mov_b32 m0, s44
	v_mfma_f32_16x16x32_bf16 v[92:95], v[166:169], v[226:229], v[92:95]
	global_load_lds_dwordx4 v2, s[64:65]
	v_mfma_f32_16x16x32_bf16 v[96:99], v[214:217], v[226:229], v[96:99]
	v_mfma_f32_16x16x32_bf16 v[36:39], v[218:221], v[226:229], v[36:39]
	ds_read_b128 v[226:229], v19
	s_waitcnt lgkmcnt(3)
	v_mfma_f32_16x16x32_bf16 v[104:107], v[158:161], v[162:165], v[104:107]
	s_waitcnt lgkmcnt(2)
	v_mfma_f32_16x16x32_bf16 v[116:119], v[158:161], v[178:181], v[116:119]
	s_waitcnt lgkmcnt(1)
	s_mov_b32 m0, s45
	v_mfma_f32_16x16x32_bf16 v[128:131], v[158:161], v[222:225], v[128:131]
	global_load_lds_dwordx4 v2, s[68:69]
	s_waitcnt lgkmcnt(0)
	v_mfma_f32_16x16x32_bf16 v[100:103], v[158:161], v[226:229], v[100:103]
	ds_read_b128 v[158:161], v20
	v_mfma_f32_16x16x32_bf16 v[108:111], v[166:169], v[162:165], v[108:111]
	v_mfma_f32_16x16x32_bf16 v[120:123], v[166:169], v[178:181], v[120:123]
	v_mfma_f32_16x16x32_bf16 v[132:135], v[166:169], v[222:225], v[132:135]
	s_mov_b32 m0, s46
	v_mfma_f32_16x16x32_bf16 v[140:143], v[166:169], v[226:229], v[140:143]
	global_load_lds_dwordx4 v4, s[64:65]
	ds_read_b128 v[166:169], v24
	v_mfma_f32_16x16x32_bf16 v[112:115], v[214:217], v[162:165], v[112:115]
	v_mfma_f32_16x16x32_bf16 v[52:55], v[218:221], v[162:165], v[52:55]
	ds_read_b128 v[162:165], v21
	v_mfma_f32_16x16x32_bf16 v[124:127], v[214:217], v[178:181], v[124:127]
	v_mfma_f32_16x16x32_bf16 v[68:71], v[218:221], v[178:181], v[68:71]
	ds_read_b128 v[178:181], v25
	s_mov_b32 m0, s47
	v_mfma_f32_16x16x32_bf16 v[136:139], v[214:217], v[222:225], v[136:139]
	global_load_lds_dwordx4 v4, s[68:69]
	v_mfma_f32_16x16x32_bf16 v[84:87], v[218:221], v[222:225], v[84:87]
	ds_read_b128 v[222:225], v26
	v_mfma_f32_16x16x32_bf16 v[150:153], v[214:217], v[226:229], v[150:153]
	ds_read_b128 v[214:217], v23
	v_mfma_f32_16x16x32_bf16 v[154:157], v[218:221], v[226:229], v[154:157]
	ds_read_b128 v[218:221], v22
	ds_read_b128 v[226:229], v27
	s_waitcnt lgkmcnt(6)
	v_mfma_f32_16x16x32_bf16 v[40:43], v[158:161], v[166:169], v[40:43]
	s_waitcnt lgkmcnt(5)
	s_mov_b32 m0, s49
	v_mfma_f32_16x16x32_bf16 v[44:47], v[162:165], v[166:169], v[44:47]
	global_load_lds_dwordx4 v146, s[64:65]
	s_waitcnt lgkmcnt(4)
	v_mfma_f32_16x16x32_bf16 v[56:59], v[158:161], v[178:181], v[56:59]
	v_mfma_f32_16x16x32_bf16 v[60:63], v[162:165], v[178:181], v[60:63]
	s_waitcnt lgkmcnt(3)
	v_mfma_f32_16x16x32_bf16 v[72:75], v[158:161], v[222:225], v[72:75]
	v_mfma_f32_16x16x32_bf16 v[76:79], v[162:165], v[222:225], v[76:79]
	s_waitcnt lgkmcnt(2)
	s_mov_b32 m0, s50
	v_mfma_f32_16x16x32_bf16 v[48:51], v[214:217], v[166:169], v[48:51]
	global_load_lds_dwordx4 v146, s[68:69]
	s_waitcnt lgkmcnt(1)
	v_mfma_f32_16x16x32_bf16 v[174:177], v[218:221], v[166:169], v[174:177]
	ds_read_b128 v[166:169], v28
	v_mfma_f32_16x16x32_bf16 v[64:67], v[214:217], v[178:181], v[64:67]
	v_mfma_f32_16x16x32_bf16 v[170:173], v[218:221], v[178:181], v[170:173]
	ds_read_b128 v[178:181], v29
	v_mfma_f32_16x16x32_bf16 v[80:83], v[214:217], v[222:225], v[80:83]
	v_mfma_f32_16x16x32_bf16 v[32:35], v[218:221], v[222:225], v[32:35]
	ds_read_b128 v[222:225], v30
	s_waitcnt lgkmcnt(3)
	v_mfma_f32_16x16x32_bf16 v[88:91], v[158:161], v[226:229], v[88:91]
	v_mfma_f32_16x16x32_bf16 v[92:95], v[162:165], v[226:229], v[92:95]
	v_mfma_f32_16x16x32_bf16 v[96:99], v[214:217], v[226:229], v[96:99]
	v_mfma_f32_16x16x32_bf16 v[36:39], v[218:221], v[226:229], v[36:39]
	ds_read_b128 v[226:229], v31
	s_waitcnt lgkmcnt(3)
	v_mfma_f32_16x16x32_bf16 v[104:107], v[158:161], v[166:169], v[104:107]
	v_mfma_f32_16x16x32_bf16 v[108:111], v[162:165], v[166:169], v[108:111]
	v_mfma_f32_16x16x32_bf16 v[112:115], v[214:217], v[166:169], v[112:115]
	v_mfma_f32_16x16x32_bf16 v[52:55], v[218:221], v[166:169], v[52:55]
	s_waitcnt lgkmcnt(2)
	v_mfma_f32_16x16x32_bf16 v[116:119], v[158:161], v[178:181], v[116:119]
	v_mfma_f32_16x16x32_bf16 v[120:123], v[162:165], v[178:181], v[120:123]
	v_mfma_f32_16x16x32_bf16 v[124:127], v[214:217], v[178:181], v[124:127]
	v_mfma_f32_16x16x32_bf16 v[68:71], v[218:221], v[178:181], v[68:71]
	s_waitcnt lgkmcnt(1)
	v_mfma_f32_16x16x32_bf16 v[128:131], v[158:161], v[222:225], v[128:131]
	v_mfma_f32_16x16x32_bf16 v[132:135], v[162:165], v[222:225], v[132:135]
	v_mfma_f32_16x16x32_bf16 v[136:139], v[214:217], v[222:225], v[136:139]
	v_mfma_f32_16x16x32_bf16 v[84:87], v[218:221], v[222:225], v[84:87]
	s_waitcnt lgkmcnt(0)
	v_mfma_f32_16x16x32_bf16 v[100:103], v[158:161], v[226:229], v[100:103]
	v_mfma_f32_16x16x32_bf16 v[140:143], v[162:165], v[226:229], v[140:143]
	v_mfma_f32_16x16x32_bf16 v[150:153], v[214:217], v[226:229], v[150:153]
	v_mfma_f32_16x16x32_bf16 v[154:157], v[218:221], v[226:229], v[154:157]
	s_add_u32 s64, s0, 0x1d80
	s_addc_u32 s65, s1, 0
	s_add_u32 s68, s14, 0x1d80
	s_waitcnt vmcnt(0)
	s_barrier
	s_addc_u32 s69, s15, 0
	ds_read_b128 v[158:161], v7 offset:32768
	ds_read_b128 v[162:165], v6
	ds_read_b128 v[166:169], v7 offset:34816
	ds_read_b128 v[178:181], v6 offset:2048
	ds_read_b128 v[214:217], v7 offset:36864
	ds_read_b128 v[218:221], v7 offset:38912
	ds_read_b128 v[222:225], v6 offset:4096
	ds_read_b128 v[226:229], v6 offset:6144
	s_waitcnt lgkmcnt(6)
	v_mfma_f32_16x16x32_bf16 v[40:43], v[158:161], v[162:165], v[40:43]
	s_waitcnt lgkmcnt(5)
	v_mfma_f32_16x16x32_bf16 v[44:47], v[166:169], v[162:165], v[44:47]
	s_waitcnt lgkmcnt(4)
	v_mfma_f32_16x16x32_bf16 v[56:59], v[158:161], v[178:181], v[56:59]
	s_mov_b32 m0, s52
	v_mfma_f32_16x16x32_bf16 v[60:63], v[166:169], v[178:181], v[60:63]
	global_load_lds_dwordx4 v0, s[64:65]
	s_waitcnt lgkmcnt(3)
	v_mfma_f32_16x16x32_bf16 v[48:51], v[214:217], v[162:165], v[48:51]
	v_mfma_f32_16x16x32_bf16 v[64:67], v[214:217], v[178:181], v[64:67]
	s_waitcnt lgkmcnt(2)
	v_mfma_f32_16x16x32_bf16 v[174:177], v[218:221], v[162:165], v[174:177]
	ds_read_b128 v[162:165], v6 offset:8192
	v_mfma_f32_16x16x32_bf16 v[170:173], v[218:221], v[178:181], v[170:173]
	ds_read_b128 v[178:181], v6 offset:10240
	s_waitcnt lgkmcnt(3)
	s_mov_b32 m0, s51
	v_mfma_f32_16x16x32_bf16 v[72:75], v[158:161], v[222:225], v[72:75]
	global_load_lds_dwordx4 v0, s[68:69]
	v_mfma_f32_16x16x32_bf16 v[76:79], v[166:169], v[222:225], v[76:79]
	v_mfma_f32_16x16x32_bf16 v[80:83], v[214:217], v[222:225], v[80:83]
	v_mfma_f32_16x16x32_bf16 v[32:35], v[218:221], v[222:225], v[32:35]
	ds_read_b128 v[222:225], v6 offset:12288
	s_waitcnt lgkmcnt(3)
	v_mfma_f32_16x16x32_bf16 v[88:91], v[158:161], v[226:229], v[88:91]
	s_mov_b32 m0, s53
	v_mfma_f32_16x16x32_bf16 v[92:95], v[166:169], v[226:229], v[92:95]
	global_load_lds_dwordx4 v2, s[64:65]
	v_mfma_f32_16x16x32_bf16 v[96:99], v[214:217], v[226:229], v[96:99]
	v_mfma_f32_16x16x32_bf16 v[36:39], v[218:221], v[226:229], v[36:39]
	ds_read_b128 v[226:229], v6 offset:14336
	s_waitcnt lgkmcnt(3)
	v_mfma_f32_16x16x32_bf16 v[104:107], v[158:161], v[162:165], v[104:107]
	s_waitcnt lgkmcnt(2)
	v_mfma_f32_16x16x32_bf16 v[116:119], v[158:161], v[178:181], v[116:119]
	s_waitcnt lgkmcnt(1)
	s_mov_b32 m0, s54
	v_mfma_f32_16x16x32_bf16 v[128:131], v[158:161], v[222:225], v[128:131]
	global_load_lds_dwordx4 v2, s[68:69]
	s_waitcnt lgkmcnt(0)
	v_mfma_f32_16x16x32_bf16 v[100:103], v[158:161], v[226:229], v[100:103]
	ds_read_b128 v[158:161], v7 offset:33792
	v_mfma_f32_16x16x32_bf16 v[108:111], v[166:169], v[162:165], v[108:111]
	v_mfma_f32_16x16x32_bf16 v[120:123], v[166:169], v[178:181], v[120:123]
	v_mfma_f32_16x16x32_bf16 v[132:135], v[166:169], v[222:225], v[132:135]
	s_mov_b32 m0, s55
	v_mfma_f32_16x16x32_bf16 v[140:143], v[166:169], v[226:229], v[140:143]
	global_load_lds_dwordx4 v4, s[64:65]
	ds_read_b128 v[166:169], v6 offset:1024
	v_mfma_f32_16x16x32_bf16 v[112:115], v[214:217], v[162:165], v[112:115]
	v_mfma_f32_16x16x32_bf16 v[52:55], v[218:221], v[162:165], v[52:55]
	ds_read_b128 v[162:165], v7 offset:35840
	v_mfma_f32_16x16x32_bf16 v[124:127], v[214:217], v[178:181], v[124:127]
	v_mfma_f32_16x16x32_bf16 v[68:71], v[218:221], v[178:181], v[68:71]
	ds_read_b128 v[178:181], v6 offset:3072
	s_mov_b32 m0, s58
	v_mfma_f32_16x16x32_bf16 v[136:139], v[214:217], v[222:225], v[136:139]
	global_load_lds_dwordx4 v4, s[68:69]
	v_mfma_f32_16x16x32_bf16 v[84:87], v[218:221], v[222:225], v[84:87]
	ds_read_b128 v[222:225], v6 offset:5120
	v_mfma_f32_16x16x32_bf16 v[150:153], v[214:217], v[226:229], v[150:153]
	ds_read_b128 v[214:217], v7 offset:37888
	v_mfma_f32_16x16x32_bf16 v[154:157], v[218:221], v[226:229], v[154:157]
	ds_read_b128 v[218:221], v7 offset:39936
	ds_read_b128 v[226:229], v6 offset:7168
	s_waitcnt lgkmcnt(6)
	v_mfma_f32_16x16x32_bf16 v[40:43], v[158:161], v[166:169], v[40:43]
	s_waitcnt lgkmcnt(5)
	s_mov_b32 m0, s62
	v_mfma_f32_16x16x32_bf16 v[44:47], v[162:165], v[166:169], v[44:47]
	global_load_lds_dwordx4 v146, s[64:65]
	s_waitcnt lgkmcnt(4)
	v_mfma_f32_16x16x32_bf16 v[56:59], v[158:161], v[178:181], v[56:59]
	v_mfma_f32_16x16x32_bf16 v[60:63], v[162:165], v[178:181], v[60:63]
	s_waitcnt lgkmcnt(3)
	v_mfma_f32_16x16x32_bf16 v[72:75], v[158:161], v[222:225], v[72:75]
	v_mfma_f32_16x16x32_bf16 v[76:79], v[162:165], v[222:225], v[76:79]
	s_waitcnt lgkmcnt(2)
	s_mov_b32 m0, s63
	v_mfma_f32_16x16x32_bf16 v[48:51], v[214:217], v[166:169], v[48:51]
	global_load_lds_dwordx4 v146, s[68:69]
	s_waitcnt lgkmcnt(1)
	v_mfma_f32_16x16x32_bf16 v[174:177], v[218:221], v[166:169], v[174:177]
	ds_read_b128 v[166:169], v6 offset:9216
	v_mfma_f32_16x16x32_bf16 v[64:67], v[214:217], v[178:181], v[64:67]
	v_mfma_f32_16x16x32_bf16 v[170:173], v[218:221], v[178:181], v[170:173]
	ds_read_b128 v[178:181], v6 offset:11264
	v_mfma_f32_16x16x32_bf16 v[80:83], v[214:217], v[222:225], v[80:83]
	v_mfma_f32_16x16x32_bf16 v[32:35], v[218:221], v[222:225], v[32:35]
	ds_read_b128 v[222:225], v6 offset:13312
	s_waitcnt lgkmcnt(3)
	v_mfma_f32_16x16x32_bf16 v[88:91], v[158:161], v[226:229], v[88:91]
	v_mfma_f32_16x16x32_bf16 v[92:95], v[162:165], v[226:229], v[92:95]
	v_mfma_f32_16x16x32_bf16 v[96:99], v[214:217], v[226:229], v[96:99]
	v_mfma_f32_16x16x32_bf16 v[36:39], v[218:221], v[226:229], v[36:39]
	ds_read_b128 v[226:229], v6 offset:15360
	s_waitcnt lgkmcnt(3)
	v_mfma_f32_16x16x32_bf16 v[104:107], v[158:161], v[166:169], v[104:107]
	v_mfma_f32_16x16x32_bf16 v[108:111], v[162:165], v[166:169], v[108:111]
	v_mfma_f32_16x16x32_bf16 v[112:115], v[214:217], v[166:169], v[112:115]
	v_mfma_f32_16x16x32_bf16 v[52:55], v[218:221], v[166:169], v[52:55]
	s_waitcnt lgkmcnt(2)
	v_mfma_f32_16x16x32_bf16 v[116:119], v[158:161], v[178:181], v[116:119]
	v_mfma_f32_16x16x32_bf16 v[120:123], v[162:165], v[178:181], v[120:123]
	v_mfma_f32_16x16x32_bf16 v[124:127], v[214:217], v[178:181], v[124:127]
	v_mfma_f32_16x16x32_bf16 v[68:71], v[218:221], v[178:181], v[68:71]
	s_waitcnt lgkmcnt(1)
	v_mfma_f32_16x16x32_bf16 v[128:131], v[158:161], v[222:225], v[128:131]
	v_mfma_f32_16x16x32_bf16 v[132:135], v[162:165], v[222:225], v[132:135]
	v_mfma_f32_16x16x32_bf16 v[136:139], v[214:217], v[222:225], v[136:139]
	v_mfma_f32_16x16x32_bf16 v[84:87], v[218:221], v[222:225], v[84:87]
	s_waitcnt lgkmcnt(0)
	v_mfma_f32_16x16x32_bf16 v[100:103], v[158:161], v[226:229], v[100:103]
	v_mfma_f32_16x16x32_bf16 v[140:143], v[162:165], v[226:229], v[140:143]
	v_mfma_f32_16x16x32_bf16 v[150:153], v[214:217], v[226:229], v[150:153]
	v_mfma_f32_16x16x32_bf16 v[154:157], v[218:221], v[226:229], v[154:157]
	s_add_u32 s64, s0, 0x1e00
	s_addc_u32 s65, s1, 0
	s_add_u32 s68, s14, 0x1e00
	s_waitcnt vmcnt(0)
	s_barrier
	s_addc_u32 s69, s15, 0
	ds_read_b128 v[158:161], v8
	ds_read_b128 v[162:165], v12
	ds_read_b128 v[166:169], v9
	ds_read_b128 v[178:181], v13
	ds_read_b128 v[214:217], v11
	ds_read_b128 v[218:221], v10
	ds_read_b128 v[222:225], v14
	ds_read_b128 v[226:229], v15
	s_waitcnt lgkmcnt(6)
	v_mfma_f32_16x16x32_bf16 v[40:43], v[158:161], v[162:165], v[40:43]
	s_waitcnt lgkmcnt(5)
	v_mfma_f32_16x16x32_bf16 v[44:47], v[166:169], v[162:165], v[44:47]
	s_waitcnt lgkmcnt(4)
	v_mfma_f32_16x16x32_bf16 v[56:59], v[158:161], v[178:181], v[56:59]
	s_mov_b32 m0, s42
	v_mfma_f32_16x16x32_bf16 v[60:63], v[166:169], v[178:181], v[60:63]
	global_load_lds_dwordx4 v0, s[64:65]
	s_waitcnt lgkmcnt(3)
	v_mfma_f32_16x16x32_bf16 v[48:51], v[214:217], v[162:165], v[48:51]
	v_mfma_f32_16x16x32_bf16 v[64:67], v[214:217], v[178:181], v[64:67]
	s_waitcnt lgkmcnt(2)
	v_mfma_f32_16x16x32_bf16 v[174:177], v[218:221], v[162:165], v[174:177]
	ds_read_b128 v[162:165], v16
	v_mfma_f32_16x16x32_bf16 v[170:173], v[218:221], v[178:181], v[170:173]
	ds_read_b128 v[178:181], v17
	s_waitcnt lgkmcnt(3)
	s_mov_b32 m0, s43
	v_mfma_f32_16x16x32_bf16 v[72:75], v[158:161], v[222:225], v[72:75]
	global_load_lds_dwordx4 v0, s[68:69]
	v_mfma_f32_16x16x32_bf16 v[76:79], v[166:169], v[222:225], v[76:79]
	v_mfma_f32_16x16x32_bf16 v[80:83], v[214:217], v[222:225], v[80:83]
	v_mfma_f32_16x16x32_bf16 v[32:35], v[218:221], v[222:225], v[32:35]
	ds_read_b128 v[222:225], v18
	s_waitcnt lgkmcnt(3)
	v_mfma_f32_16x16x32_bf16 v[88:91], v[158:161], v[226:229], v[88:91]
	s_mov_b32 m0, s44
	v_mfma_f32_16x16x32_bf16 v[92:95], v[166:169], v[226:229], v[92:95]
	global_load_lds_dwordx4 v2, s[64:65]
	v_mfma_f32_16x16x32_bf16 v[96:99], v[214:217], v[226:229], v[96:99]
	v_mfma_f32_16x16x32_bf16 v[36:39], v[218:221], v[226:229], v[36:39]
	ds_read_b128 v[226:229], v19
	s_waitcnt lgkmcnt(3)
	v_mfma_f32_16x16x32_bf16 v[104:107], v[158:161], v[162:165], v[104:107]
	s_waitcnt lgkmcnt(2)
	v_mfma_f32_16x16x32_bf16 v[116:119], v[158:161], v[178:181], v[116:119]
	s_waitcnt lgkmcnt(1)
	s_mov_b32 m0, s45
	v_mfma_f32_16x16x32_bf16 v[128:131], v[158:161], v[222:225], v[128:131]
	global_load_lds_dwordx4 v2, s[68:69]
	s_waitcnt lgkmcnt(0)
	v_mfma_f32_16x16x32_bf16 v[100:103], v[158:161], v[226:229], v[100:103]
	ds_read_b128 v[158:161], v20
	v_mfma_f32_16x16x32_bf16 v[108:111], v[166:169], v[162:165], v[108:111]
	v_mfma_f32_16x16x32_bf16 v[120:123], v[166:169], v[178:181], v[120:123]
	v_mfma_f32_16x16x32_bf16 v[132:135], v[166:169], v[222:225], v[132:135]
	s_mov_b32 m0, s46
	v_mfma_f32_16x16x32_bf16 v[140:143], v[166:169], v[226:229], v[140:143]
	global_load_lds_dwordx4 v4, s[64:65]
	ds_read_b128 v[166:169], v24
	v_mfma_f32_16x16x32_bf16 v[112:115], v[214:217], v[162:165], v[112:115]
	v_mfma_f32_16x16x32_bf16 v[52:55], v[218:221], v[162:165], v[52:55]
	ds_read_b128 v[162:165], v21
	v_mfma_f32_16x16x32_bf16 v[124:127], v[214:217], v[178:181], v[124:127]
	v_mfma_f32_16x16x32_bf16 v[68:71], v[218:221], v[178:181], v[68:71]
	ds_read_b128 v[178:181], v25
	s_mov_b32 m0, s47
	v_mfma_f32_16x16x32_bf16 v[136:139], v[214:217], v[222:225], v[136:139]
	global_load_lds_dwordx4 v4, s[68:69]
	v_mfma_f32_16x16x32_bf16 v[84:87], v[218:221], v[222:225], v[84:87]
	ds_read_b128 v[222:225], v26
	v_mfma_f32_16x16x32_bf16 v[150:153], v[214:217], v[226:229], v[150:153]
	ds_read_b128 v[214:217], v23
	v_mfma_f32_16x16x32_bf16 v[154:157], v[218:221], v[226:229], v[154:157]
	ds_read_b128 v[218:221], v22
	ds_read_b128 v[226:229], v27
	s_waitcnt lgkmcnt(6)
	v_mfma_f32_16x16x32_bf16 v[40:43], v[158:161], v[166:169], v[40:43]
	s_waitcnt lgkmcnt(5)
	s_mov_b32 m0, s49
	v_mfma_f32_16x16x32_bf16 v[44:47], v[162:165], v[166:169], v[44:47]
	global_load_lds_dwordx4 v146, s[64:65]
	s_waitcnt lgkmcnt(4)
	v_mfma_f32_16x16x32_bf16 v[56:59], v[158:161], v[178:181], v[56:59]
	v_mfma_f32_16x16x32_bf16 v[60:63], v[162:165], v[178:181], v[60:63]
	s_waitcnt lgkmcnt(3)
	v_mfma_f32_16x16x32_bf16 v[72:75], v[158:161], v[222:225], v[72:75]
	v_mfma_f32_16x16x32_bf16 v[76:79], v[162:165], v[222:225], v[76:79]
	s_waitcnt lgkmcnt(2)
	s_mov_b32 m0, s50
	v_mfma_f32_16x16x32_bf16 v[48:51], v[214:217], v[166:169], v[48:51]
	global_load_lds_dwordx4 v146, s[68:69]
	s_waitcnt lgkmcnt(1)
	v_mfma_f32_16x16x32_bf16 v[174:177], v[218:221], v[166:169], v[174:177]
	ds_read_b128 v[166:169], v28
	v_mfma_f32_16x16x32_bf16 v[64:67], v[214:217], v[178:181], v[64:67]
	v_mfma_f32_16x16x32_bf16 v[170:173], v[218:221], v[178:181], v[170:173]
	ds_read_b128 v[178:181], v29
	v_mfma_f32_16x16x32_bf16 v[80:83], v[214:217], v[222:225], v[80:83]
	v_mfma_f32_16x16x32_bf16 v[32:35], v[218:221], v[222:225], v[32:35]
	ds_read_b128 v[222:225], v30
	s_waitcnt lgkmcnt(3)
	v_mfma_f32_16x16x32_bf16 v[88:91], v[158:161], v[226:229], v[88:91]
	v_mfma_f32_16x16x32_bf16 v[92:95], v[162:165], v[226:229], v[92:95]
	v_mfma_f32_16x16x32_bf16 v[96:99], v[214:217], v[226:229], v[96:99]
	v_mfma_f32_16x16x32_bf16 v[36:39], v[218:221], v[226:229], v[36:39]
	ds_read_b128 v[226:229], v31
	s_waitcnt lgkmcnt(3)
	v_mfma_f32_16x16x32_bf16 v[104:107], v[158:161], v[166:169], v[104:107]
	v_mfma_f32_16x16x32_bf16 v[108:111], v[162:165], v[166:169], v[108:111]
	v_mfma_f32_16x16x32_bf16 v[112:115], v[214:217], v[166:169], v[112:115]
	v_mfma_f32_16x16x32_bf16 v[52:55], v[218:221], v[166:169], v[52:55]
	s_waitcnt lgkmcnt(2)
	v_mfma_f32_16x16x32_bf16 v[116:119], v[158:161], v[178:181], v[116:119]
	v_mfma_f32_16x16x32_bf16 v[120:123], v[162:165], v[178:181], v[120:123]
	v_mfma_f32_16x16x32_bf16 v[124:127], v[214:217], v[178:181], v[124:127]
	v_mfma_f32_16x16x32_bf16 v[68:71], v[218:221], v[178:181], v[68:71]
	s_waitcnt lgkmcnt(1)
	v_mfma_f32_16x16x32_bf16 v[128:131], v[158:161], v[222:225], v[128:131]
	v_mfma_f32_16x16x32_bf16 v[132:135], v[162:165], v[222:225], v[132:135]
	v_mfma_f32_16x16x32_bf16 v[136:139], v[214:217], v[222:225], v[136:139]
	v_mfma_f32_16x16x32_bf16 v[84:87], v[218:221], v[222:225], v[84:87]
	s_waitcnt lgkmcnt(0)
	v_mfma_f32_16x16x32_bf16 v[100:103], v[158:161], v[226:229], v[100:103]
	v_mfma_f32_16x16x32_bf16 v[140:143], v[162:165], v[226:229], v[140:143]
	v_mfma_f32_16x16x32_bf16 v[150:153], v[214:217], v[226:229], v[150:153]
	v_mfma_f32_16x16x32_bf16 v[154:157], v[218:221], v[226:229], v[154:157]
	s_add_u32 s64, s0, 0x1e80
	s_addc_u32 s65, s1, 0
	s_add_u32 s68, s14, 0x1e80
	s_waitcnt vmcnt(0)
	s_barrier
	s_addc_u32 s69, s15, 0
	ds_read_b128 v[158:161], v7 offset:32768
	ds_read_b128 v[162:165], v6
	ds_read_b128 v[166:169], v7 offset:34816
	ds_read_b128 v[178:181], v6 offset:2048
	ds_read_b128 v[214:217], v7 offset:36864
	ds_read_b128 v[218:221], v7 offset:38912
	ds_read_b128 v[222:225], v6 offset:4096
	ds_read_b128 v[226:229], v6 offset:6144
	s_waitcnt lgkmcnt(6)
	v_mfma_f32_16x16x32_bf16 v[40:43], v[158:161], v[162:165], v[40:43]
	s_waitcnt lgkmcnt(5)
	v_mfma_f32_16x16x32_bf16 v[44:47], v[166:169], v[162:165], v[44:47]
	s_waitcnt lgkmcnt(4)
	v_mfma_f32_16x16x32_bf16 v[56:59], v[158:161], v[178:181], v[56:59]
	s_mov_b32 m0, s52
	v_mfma_f32_16x16x32_bf16 v[60:63], v[166:169], v[178:181], v[60:63]
	global_load_lds_dwordx4 v0, s[64:65]
	s_waitcnt lgkmcnt(3)
	v_mfma_f32_16x16x32_bf16 v[48:51], v[214:217], v[162:165], v[48:51]
	v_mfma_f32_16x16x32_bf16 v[64:67], v[214:217], v[178:181], v[64:67]
	s_waitcnt lgkmcnt(2)
	v_mfma_f32_16x16x32_bf16 v[174:177], v[218:221], v[162:165], v[174:177]
	ds_read_b128 v[162:165], v6 offset:8192
	v_mfma_f32_16x16x32_bf16 v[170:173], v[218:221], v[178:181], v[170:173]
	ds_read_b128 v[178:181], v6 offset:10240
	s_waitcnt lgkmcnt(3)
	s_mov_b32 m0, s51
	v_mfma_f32_16x16x32_bf16 v[72:75], v[158:161], v[222:225], v[72:75]
	global_load_lds_dwordx4 v0, s[68:69]
	v_mfma_f32_16x16x32_bf16 v[76:79], v[166:169], v[222:225], v[76:79]
	v_mfma_f32_16x16x32_bf16 v[80:83], v[214:217], v[222:225], v[80:83]
	v_mfma_f32_16x16x32_bf16 v[32:35], v[218:221], v[222:225], v[32:35]
	ds_read_b128 v[222:225], v6 offset:12288
	s_waitcnt lgkmcnt(3)
	v_mfma_f32_16x16x32_bf16 v[88:91], v[158:161], v[226:229], v[88:91]
	s_mov_b32 m0, s53
	v_mfma_f32_16x16x32_bf16 v[92:95], v[166:169], v[226:229], v[92:95]
	global_load_lds_dwordx4 v2, s[64:65]
	v_mfma_f32_16x16x32_bf16 v[96:99], v[214:217], v[226:229], v[96:99]
	v_mfma_f32_16x16x32_bf16 v[36:39], v[218:221], v[226:229], v[36:39]
	ds_read_b128 v[226:229], v6 offset:14336
	s_waitcnt lgkmcnt(3)
	v_mfma_f32_16x16x32_bf16 v[104:107], v[158:161], v[162:165], v[104:107]
	s_waitcnt lgkmcnt(2)
	v_mfma_f32_16x16x32_bf16 v[116:119], v[158:161], v[178:181], v[116:119]
	s_waitcnt lgkmcnt(1)
	s_mov_b32 m0, s54
	v_mfma_f32_16x16x32_bf16 v[128:131], v[158:161], v[222:225], v[128:131]
	global_load_lds_dwordx4 v2, s[68:69]
	s_waitcnt lgkmcnt(0)
	v_mfma_f32_16x16x32_bf16 v[100:103], v[158:161], v[226:229], v[100:103]
	ds_read_b128 v[158:161], v7 offset:33792
	v_mfma_f32_16x16x32_bf16 v[108:111], v[166:169], v[162:165], v[108:111]
	v_mfma_f32_16x16x32_bf16 v[120:123], v[166:169], v[178:181], v[120:123]
	v_mfma_f32_16x16x32_bf16 v[132:135], v[166:169], v[222:225], v[132:135]
	s_mov_b32 m0, s55
	v_mfma_f32_16x16x32_bf16 v[140:143], v[166:169], v[226:229], v[140:143]
	global_load_lds_dwordx4 v4, s[64:65]
	ds_read_b128 v[166:169], v6 offset:1024
	v_mfma_f32_16x16x32_bf16 v[112:115], v[214:217], v[162:165], v[112:115]
	v_mfma_f32_16x16x32_bf16 v[52:55], v[218:221], v[162:165], v[52:55]
	ds_read_b128 v[162:165], v7 offset:35840
	v_mfma_f32_16x16x32_bf16 v[124:127], v[214:217], v[178:181], v[124:127]
	v_mfma_f32_16x16x32_bf16 v[68:71], v[218:221], v[178:181], v[68:71]
	ds_read_b128 v[178:181], v6 offset:3072
	s_mov_b32 m0, s58
	v_mfma_f32_16x16x32_bf16 v[136:139], v[214:217], v[222:225], v[136:139]
	global_load_lds_dwordx4 v4, s[68:69]
	v_mfma_f32_16x16x32_bf16 v[84:87], v[218:221], v[222:225], v[84:87]
	ds_read_b128 v[222:225], v6 offset:5120
	v_mfma_f32_16x16x32_bf16 v[150:153], v[214:217], v[226:229], v[150:153]
	ds_read_b128 v[214:217], v7 offset:37888
	v_mfma_f32_16x16x32_bf16 v[154:157], v[218:221], v[226:229], v[154:157]
	ds_read_b128 v[218:221], v7 offset:39936
	ds_read_b128 v[226:229], v6 offset:7168
	s_waitcnt lgkmcnt(6)
	v_mfma_f32_16x16x32_bf16 v[40:43], v[158:161], v[166:169], v[40:43]
	s_waitcnt lgkmcnt(5)
	s_mov_b32 m0, s62
	v_mfma_f32_16x16x32_bf16 v[44:47], v[162:165], v[166:169], v[44:47]
	global_load_lds_dwordx4 v146, s[64:65]
	s_waitcnt lgkmcnt(4)
	v_mfma_f32_16x16x32_bf16 v[56:59], v[158:161], v[178:181], v[56:59]
	v_mfma_f32_16x16x32_bf16 v[60:63], v[162:165], v[178:181], v[60:63]
	s_waitcnt lgkmcnt(3)
	v_mfma_f32_16x16x32_bf16 v[72:75], v[158:161], v[222:225], v[72:75]
	v_mfma_f32_16x16x32_bf16 v[76:79], v[162:165], v[222:225], v[76:79]
	s_waitcnt lgkmcnt(2)
	s_mov_b32 m0, s63
	v_mfma_f32_16x16x32_bf16 v[48:51], v[214:217], v[166:169], v[48:51]
	global_load_lds_dwordx4 v146, s[68:69]
	s_waitcnt lgkmcnt(1)
	v_mfma_f32_16x16x32_bf16 v[174:177], v[218:221], v[166:169], v[174:177]
	ds_read_b128 v[166:169], v6 offset:9216
	v_mfma_f32_16x16x32_bf16 v[64:67], v[214:217], v[178:181], v[64:67]
	v_mfma_f32_16x16x32_bf16 v[170:173], v[218:221], v[178:181], v[170:173]
	ds_read_b128 v[178:181], v6 offset:11264
	v_mfma_f32_16x16x32_bf16 v[80:83], v[214:217], v[222:225], v[80:83]
	v_mfma_f32_16x16x32_bf16 v[32:35], v[218:221], v[222:225], v[32:35]
	ds_read_b128 v[222:225], v6 offset:13312
	s_waitcnt lgkmcnt(3)
	v_mfma_f32_16x16x32_bf16 v[88:91], v[158:161], v[226:229], v[88:91]
	v_mfma_f32_16x16x32_bf16 v[92:95], v[162:165], v[226:229], v[92:95]
	v_mfma_f32_16x16x32_bf16 v[96:99], v[214:217], v[226:229], v[96:99]
	v_mfma_f32_16x16x32_bf16 v[36:39], v[218:221], v[226:229], v[36:39]
	ds_read_b128 v[226:229], v6 offset:15360
	s_waitcnt lgkmcnt(3)
	v_mfma_f32_16x16x32_bf16 v[104:107], v[158:161], v[166:169], v[104:107]
	v_mfma_f32_16x16x32_bf16 v[108:111], v[162:165], v[166:169], v[108:111]
	v_mfma_f32_16x16x32_bf16 v[112:115], v[214:217], v[166:169], v[112:115]
	v_mfma_f32_16x16x32_bf16 v[52:55], v[218:221], v[166:169], v[52:55]
	s_waitcnt lgkmcnt(2)
	v_mfma_f32_16x16x32_bf16 v[116:119], v[158:161], v[178:181], v[116:119]
	v_mfma_f32_16x16x32_bf16 v[120:123], v[162:165], v[178:181], v[120:123]
	v_mfma_f32_16x16x32_bf16 v[124:127], v[214:217], v[178:181], v[124:127]
	v_mfma_f32_16x16x32_bf16 v[68:71], v[218:221], v[178:181], v[68:71]
	s_waitcnt lgkmcnt(1)
	v_mfma_f32_16x16x32_bf16 v[128:131], v[158:161], v[222:225], v[128:131]
	v_mfma_f32_16x16x32_bf16 v[132:135], v[162:165], v[222:225], v[132:135]
	v_mfma_f32_16x16x32_bf16 v[136:139], v[214:217], v[222:225], v[136:139]
	v_mfma_f32_16x16x32_bf16 v[84:87], v[218:221], v[222:225], v[84:87]
	s_waitcnt lgkmcnt(0)
	v_mfma_f32_16x16x32_bf16 v[100:103], v[158:161], v[226:229], v[100:103]
	v_mfma_f32_16x16x32_bf16 v[140:143], v[162:165], v[226:229], v[140:143]
	v_mfma_f32_16x16x32_bf16 v[150:153], v[214:217], v[226:229], v[150:153]
	v_mfma_f32_16x16x32_bf16 v[154:157], v[218:221], v[226:229], v[154:157]
	s_add_u32 s64, s0, 0x1f00
	s_addc_u32 s65, s1, 0
	s_add_u32 s68, s14, 0x1f00
	s_waitcnt vmcnt(0)
	s_barrier
	s_addc_u32 s69, s15, 0
	ds_read_b128 v[158:161], v8
	ds_read_b128 v[162:165], v12
	ds_read_b128 v[166:169], v9
	ds_read_b128 v[178:181], v13
	ds_read_b128 v[214:217], v11
	ds_read_b128 v[218:221], v10
	ds_read_b128 v[222:225], v14
	ds_read_b128 v[226:229], v15
	s_waitcnt lgkmcnt(6)
	v_mfma_f32_16x16x32_bf16 v[40:43], v[158:161], v[162:165], v[40:43]
	s_waitcnt lgkmcnt(5)
	v_mfma_f32_16x16x32_bf16 v[44:47], v[166:169], v[162:165], v[44:47]
	s_waitcnt lgkmcnt(4)
	v_mfma_f32_16x16x32_bf16 v[56:59], v[158:161], v[178:181], v[56:59]
	s_mov_b32 m0, s42
	v_mfma_f32_16x16x32_bf16 v[60:63], v[166:169], v[178:181], v[60:63]
	global_load_lds_dwordx4 v0, s[64:65]
	s_waitcnt lgkmcnt(3)
	v_mfma_f32_16x16x32_bf16 v[48:51], v[214:217], v[162:165], v[48:51]
	v_mfma_f32_16x16x32_bf16 v[64:67], v[214:217], v[178:181], v[64:67]
	s_waitcnt lgkmcnt(2)
	v_mfma_f32_16x16x32_bf16 v[174:177], v[218:221], v[162:165], v[174:177]
	ds_read_b128 v[162:165], v16
	v_mfma_f32_16x16x32_bf16 v[170:173], v[218:221], v[178:181], v[170:173]
	ds_read_b128 v[178:181], v17
	s_waitcnt lgkmcnt(3)
	s_mov_b32 m0, s43
	v_mfma_f32_16x16x32_bf16 v[72:75], v[158:161], v[222:225], v[72:75]
	global_load_lds_dwordx4 v0, s[68:69]
	v_mfma_f32_16x16x32_bf16 v[76:79], v[166:169], v[222:225], v[76:79]
	v_mfma_f32_16x16x32_bf16 v[80:83], v[214:217], v[222:225], v[80:83]
	v_mfma_f32_16x16x32_bf16 v[32:35], v[218:221], v[222:225], v[32:35]
	ds_read_b128 v[222:225], v18
	s_waitcnt lgkmcnt(3)
	v_mfma_f32_16x16x32_bf16 v[88:91], v[158:161], v[226:229], v[88:91]
	s_mov_b32 m0, s44
	v_mfma_f32_16x16x32_bf16 v[92:95], v[166:169], v[226:229], v[92:95]
	global_load_lds_dwordx4 v2, s[64:65]
	v_mfma_f32_16x16x32_bf16 v[96:99], v[214:217], v[226:229], v[96:99]
	v_mfma_f32_16x16x32_bf16 v[36:39], v[218:221], v[226:229], v[36:39]
	ds_read_b128 v[226:229], v19
	s_waitcnt lgkmcnt(3)
	v_mfma_f32_16x16x32_bf16 v[104:107], v[158:161], v[162:165], v[104:107]
	s_waitcnt lgkmcnt(2)
	v_mfma_f32_16x16x32_bf16 v[116:119], v[158:161], v[178:181], v[116:119]
	s_waitcnt lgkmcnt(1)
	s_mov_b32 m0, s45
	v_mfma_f32_16x16x32_bf16 v[128:131], v[158:161], v[222:225], v[128:131]
	global_load_lds_dwordx4 v2, s[68:69]
	s_waitcnt lgkmcnt(0)
	v_mfma_f32_16x16x32_bf16 v[100:103], v[158:161], v[226:229], v[100:103]
	ds_read_b128 v[158:161], v20
	v_mfma_f32_16x16x32_bf16 v[108:111], v[166:169], v[162:165], v[108:111]
	v_mfma_f32_16x16x32_bf16 v[120:123], v[166:169], v[178:181], v[120:123]
	v_mfma_f32_16x16x32_bf16 v[132:135], v[166:169], v[222:225], v[132:135]
	s_mov_b32 m0, s46
	v_mfma_f32_16x16x32_bf16 v[140:143], v[166:169], v[226:229], v[140:143]
	global_load_lds_dwordx4 v4, s[64:65]
	ds_read_b128 v[166:169], v24
	v_mfma_f32_16x16x32_bf16 v[112:115], v[214:217], v[162:165], v[112:115]
	v_mfma_f32_16x16x32_bf16 v[52:55], v[218:221], v[162:165], v[52:55]
	ds_read_b128 v[162:165], v21
	v_mfma_f32_16x16x32_bf16 v[124:127], v[214:217], v[178:181], v[124:127]
	v_mfma_f32_16x16x32_bf16 v[68:71], v[218:221], v[178:181], v[68:71]
	ds_read_b128 v[178:181], v25
	s_mov_b32 m0, s47
	v_mfma_f32_16x16x32_bf16 v[136:139], v[214:217], v[222:225], v[136:139]
	global_load_lds_dwordx4 v4, s[68:69]
	v_mfma_f32_16x16x32_bf16 v[84:87], v[218:221], v[222:225], v[84:87]
	ds_read_b128 v[222:225], v26
	v_mfma_f32_16x16x32_bf16 v[150:153], v[214:217], v[226:229], v[150:153]
	ds_read_b128 v[214:217], v23
	v_mfma_f32_16x16x32_bf16 v[154:157], v[218:221], v[226:229], v[154:157]
	ds_read_b128 v[218:221], v22
	ds_read_b128 v[226:229], v27
	s_waitcnt lgkmcnt(6)
	v_mfma_f32_16x16x32_bf16 v[40:43], v[158:161], v[166:169], v[40:43]
	s_waitcnt lgkmcnt(5)
	s_mov_b32 m0, s49
	v_mfma_f32_16x16x32_bf16 v[44:47], v[162:165], v[166:169], v[44:47]
	global_load_lds_dwordx4 v146, s[64:65]
	s_waitcnt lgkmcnt(4)
	v_mfma_f32_16x16x32_bf16 v[56:59], v[158:161], v[178:181], v[56:59]
	v_mfma_f32_16x16x32_bf16 v[60:63], v[162:165], v[178:181], v[60:63]
	s_waitcnt lgkmcnt(3)
	v_mfma_f32_16x16x32_bf16 v[72:75], v[158:161], v[222:225], v[72:75]
	v_mfma_f32_16x16x32_bf16 v[76:79], v[162:165], v[222:225], v[76:79]
	s_waitcnt lgkmcnt(2)
	s_mov_b32 m0, s50
	v_mfma_f32_16x16x32_bf16 v[48:51], v[214:217], v[166:169], v[48:51]
	global_load_lds_dwordx4 v146, s[68:69]
	s_waitcnt lgkmcnt(1)
	v_mfma_f32_16x16x32_bf16 v[174:177], v[218:221], v[166:169], v[174:177]
	ds_read_b128 v[166:169], v28
	v_mfma_f32_16x16x32_bf16 v[64:67], v[214:217], v[178:181], v[64:67]
	v_mfma_f32_16x16x32_bf16 v[170:173], v[218:221], v[178:181], v[170:173]
	ds_read_b128 v[178:181], v29
	v_mfma_f32_16x16x32_bf16 v[80:83], v[214:217], v[222:225], v[80:83]
	v_mfma_f32_16x16x32_bf16 v[32:35], v[218:221], v[222:225], v[32:35]
	ds_read_b128 v[222:225], v30
	s_waitcnt lgkmcnt(3)
	v_mfma_f32_16x16x32_bf16 v[88:91], v[158:161], v[226:229], v[88:91]
	v_mfma_f32_16x16x32_bf16 v[92:95], v[162:165], v[226:229], v[92:95]
	v_mfma_f32_16x16x32_bf16 v[96:99], v[214:217], v[226:229], v[96:99]
	v_mfma_f32_16x16x32_bf16 v[36:39], v[218:221], v[226:229], v[36:39]
	ds_read_b128 v[226:229], v31
	s_waitcnt lgkmcnt(3)
	v_mfma_f32_16x16x32_bf16 v[104:107], v[158:161], v[166:169], v[104:107]
	v_mfma_f32_16x16x32_bf16 v[108:111], v[162:165], v[166:169], v[108:111]
	v_mfma_f32_16x16x32_bf16 v[112:115], v[214:217], v[166:169], v[112:115]
	v_mfma_f32_16x16x32_bf16 v[52:55], v[218:221], v[166:169], v[52:55]
	s_waitcnt lgkmcnt(2)
	v_mfma_f32_16x16x32_bf16 v[116:119], v[158:161], v[178:181], v[116:119]
	v_mfma_f32_16x16x32_bf16 v[120:123], v[162:165], v[178:181], v[120:123]
	v_mfma_f32_16x16x32_bf16 v[124:127], v[214:217], v[178:181], v[124:127]
	v_mfma_f32_16x16x32_bf16 v[68:71], v[218:221], v[178:181], v[68:71]
	s_waitcnt lgkmcnt(1)
	v_mfma_f32_16x16x32_bf16 v[128:131], v[158:161], v[222:225], v[128:131]
	v_mfma_f32_16x16x32_bf16 v[132:135], v[162:165], v[222:225], v[132:135]
	v_mfma_f32_16x16x32_bf16 v[136:139], v[214:217], v[222:225], v[136:139]
	v_mfma_f32_16x16x32_bf16 v[84:87], v[218:221], v[222:225], v[84:87]
	s_waitcnt lgkmcnt(0)
	v_mfma_f32_16x16x32_bf16 v[100:103], v[158:161], v[226:229], v[100:103]
	v_mfma_f32_16x16x32_bf16 v[140:143], v[162:165], v[226:229], v[140:143]
	v_mfma_f32_16x16x32_bf16 v[150:153], v[214:217], v[226:229], v[150:153]
	v_mfma_f32_16x16x32_bf16 v[154:157], v[218:221], v[226:229], v[154:157]
	s_add_u32 s64, s0, 0x1f80
	s_addc_u32 s65, s1, 0
	s_add_u32 s68, s14, 0x1f80
	s_waitcnt vmcnt(0)
	s_barrier
	s_addc_u32 s69, s15, 0
	ds_read_b128 v[158:161], v7 offset:32768
	ds_read_b128 v[162:165], v6
	ds_read_b128 v[166:169], v7 offset:34816
	ds_read_b128 v[178:181], v6 offset:2048
	ds_read_b128 v[214:217], v7 offset:36864
	ds_read_b128 v[218:221], v7 offset:38912
	ds_read_b128 v[222:225], v6 offset:4096
	ds_read_b128 v[226:229], v6 offset:6144
	s_waitcnt lgkmcnt(6)
	v_mfma_f32_16x16x32_bf16 v[40:43], v[158:161], v[162:165], v[40:43]
	s_waitcnt lgkmcnt(5)
	v_mfma_f32_16x16x32_bf16 v[44:47], v[166:169], v[162:165], v[44:47]
	s_waitcnt lgkmcnt(4)
	v_mfma_f32_16x16x32_bf16 v[56:59], v[158:161], v[178:181], v[56:59]
	s_mov_b32 m0, s52
	v_mfma_f32_16x16x32_bf16 v[60:63], v[166:169], v[178:181], v[60:63]
	global_load_lds_dwordx4 v0, s[64:65]
	s_waitcnt lgkmcnt(3)
	v_mfma_f32_16x16x32_bf16 v[48:51], v[214:217], v[162:165], v[48:51]
	v_mfma_f32_16x16x32_bf16 v[64:67], v[214:217], v[178:181], v[64:67]
	s_waitcnt lgkmcnt(2)
	v_mfma_f32_16x16x32_bf16 v[174:177], v[218:221], v[162:165], v[174:177]
	ds_read_b128 v[162:165], v6 offset:8192
	v_mfma_f32_16x16x32_bf16 v[170:173], v[218:221], v[178:181], v[170:173]
	ds_read_b128 v[178:181], v6 offset:10240
	s_waitcnt lgkmcnt(3)
	s_mov_b32 m0, s51
	v_mfma_f32_16x16x32_bf16 v[72:75], v[158:161], v[222:225], v[72:75]
	global_load_lds_dwordx4 v0, s[68:69]
	v_mfma_f32_16x16x32_bf16 v[76:79], v[166:169], v[222:225], v[76:79]
	v_mfma_f32_16x16x32_bf16 v[80:83], v[214:217], v[222:225], v[80:83]
	v_mfma_f32_16x16x32_bf16 v[32:35], v[218:221], v[222:225], v[32:35]
	ds_read_b128 v[222:225], v6 offset:12288
	s_waitcnt lgkmcnt(3)
	v_mfma_f32_16x16x32_bf16 v[88:91], v[158:161], v[226:229], v[88:91]
	s_mov_b32 m0, s53
	v_mfma_f32_16x16x32_bf16 v[92:95], v[166:169], v[226:229], v[92:95]
	global_load_lds_dwordx4 v2, s[64:65]
	v_mfma_f32_16x16x32_bf16 v[96:99], v[214:217], v[226:229], v[96:99]
	v_mfma_f32_16x16x32_bf16 v[36:39], v[218:221], v[226:229], v[36:39]
	ds_read_b128 v[226:229], v6 offset:14336
	s_waitcnt lgkmcnt(3)
	v_mfma_f32_16x16x32_bf16 v[104:107], v[158:161], v[162:165], v[104:107]
	s_waitcnt lgkmcnt(2)
	v_mfma_f32_16x16x32_bf16 v[116:119], v[158:161], v[178:181], v[116:119]
	s_waitcnt lgkmcnt(1)
	s_mov_b32 m0, s54
	v_mfma_f32_16x16x32_bf16 v[128:131], v[158:161], v[222:225], v[128:131]
	global_load_lds_dwordx4 v2, s[68:69]
	s_waitcnt lgkmcnt(0)
	v_mfma_f32_16x16x32_bf16 v[100:103], v[158:161], v[226:229], v[100:103]
	ds_read_b128 v[158:161], v7 offset:33792
	v_mfma_f32_16x16x32_bf16 v[108:111], v[166:169], v[162:165], v[108:111]
	v_mfma_f32_16x16x32_bf16 v[120:123], v[166:169], v[178:181], v[120:123]
	v_mfma_f32_16x16x32_bf16 v[132:135], v[166:169], v[222:225], v[132:135]
	s_mov_b32 m0, s55
	v_mfma_f32_16x16x32_bf16 v[140:143], v[166:169], v[226:229], v[140:143]
	global_load_lds_dwordx4 v4, s[64:65]
	ds_read_b128 v[166:169], v6 offset:1024
	v_mfma_f32_16x16x32_bf16 v[112:115], v[214:217], v[162:165], v[112:115]
	v_mfma_f32_16x16x32_bf16 v[52:55], v[218:221], v[162:165], v[52:55]
	ds_read_b128 v[162:165], v7 offset:35840
	v_mfma_f32_16x16x32_bf16 v[124:127], v[214:217], v[178:181], v[124:127]
	v_mfma_f32_16x16x32_bf16 v[68:71], v[218:221], v[178:181], v[68:71]
	ds_read_b128 v[178:181], v6 offset:3072
	s_mov_b32 m0, s58
	v_mfma_f32_16x16x32_bf16 v[136:139], v[214:217], v[222:225], v[136:139]
	global_load_lds_dwordx4 v4, s[68:69]
	v_mfma_f32_16x16x32_bf16 v[84:87], v[218:221], v[222:225], v[84:87]
	ds_read_b128 v[222:225], v6 offset:5120
	v_mfma_f32_16x16x32_bf16 v[150:153], v[214:217], v[226:229], v[150:153]
	ds_read_b128 v[214:217], v7 offset:37888
	v_mfma_f32_16x16x32_bf16 v[154:157], v[218:221], v[226:229], v[154:157]
	ds_read_b128 v[218:221], v7 offset:39936
	ds_read_b128 v[226:229], v6 offset:7168
	s_waitcnt lgkmcnt(6)
	v_mfma_f32_16x16x32_bf16 v[40:43], v[158:161], v[166:169], v[40:43]
	s_waitcnt lgkmcnt(5)
	s_mov_b32 m0, s62
	v_mfma_f32_16x16x32_bf16 v[44:47], v[162:165], v[166:169], v[44:47]
	global_load_lds_dwordx4 v146, s[64:65]
	s_waitcnt lgkmcnt(4)
	v_mfma_f32_16x16x32_bf16 v[56:59], v[158:161], v[178:181], v[56:59]
	v_mfma_f32_16x16x32_bf16 v[60:63], v[162:165], v[178:181], v[60:63]
	s_waitcnt lgkmcnt(3)
	v_mfma_f32_16x16x32_bf16 v[72:75], v[158:161], v[222:225], v[72:75]
	v_mfma_f32_16x16x32_bf16 v[76:79], v[162:165], v[222:225], v[76:79]
	s_waitcnt lgkmcnt(2)
	s_mov_b32 m0, s63
	v_mfma_f32_16x16x32_bf16 v[48:51], v[214:217], v[166:169], v[48:51]
	global_load_lds_dwordx4 v146, s[68:69]
	s_waitcnt lgkmcnt(1)
	v_mfma_f32_16x16x32_bf16 v[174:177], v[218:221], v[166:169], v[174:177]
	ds_read_b128 v[166:169], v6 offset:9216
	v_mfma_f32_16x16x32_bf16 v[64:67], v[214:217], v[178:181], v[64:67]
	v_mfma_f32_16x16x32_bf16 v[170:173], v[218:221], v[178:181], v[170:173]
	ds_read_b128 v[178:181], v6 offset:11264
	v_mfma_f32_16x16x32_bf16 v[80:83], v[214:217], v[222:225], v[80:83]
	v_mfma_f32_16x16x32_bf16 v[32:35], v[218:221], v[222:225], v[32:35]
	ds_read_b128 v[222:225], v6 offset:13312
	s_waitcnt lgkmcnt(3)
	v_mfma_f32_16x16x32_bf16 v[88:91], v[158:161], v[226:229], v[88:91]
	v_mfma_f32_16x16x32_bf16 v[92:95], v[162:165], v[226:229], v[92:95]
	v_mfma_f32_16x16x32_bf16 v[96:99], v[214:217], v[226:229], v[96:99]
	v_mfma_f32_16x16x32_bf16 v[36:39], v[218:221], v[226:229], v[36:39]
	ds_read_b128 v[226:229], v6 offset:15360
	s_waitcnt lgkmcnt(3)
	v_mfma_f32_16x16x32_bf16 v[104:107], v[158:161], v[166:169], v[104:107]
	v_mfma_f32_16x16x32_bf16 v[108:111], v[162:165], v[166:169], v[108:111]
	v_mfma_f32_16x16x32_bf16 v[112:115], v[214:217], v[166:169], v[112:115]
	v_mfma_f32_16x16x32_bf16 v[52:55], v[218:221], v[166:169], v[52:55]
	s_waitcnt lgkmcnt(2)
	v_mfma_f32_16x16x32_bf16 v[116:119], v[158:161], v[178:181], v[116:119]
	v_mfma_f32_16x16x32_bf16 v[120:123], v[162:165], v[178:181], v[120:123]
	v_mfma_f32_16x16x32_bf16 v[124:127], v[214:217], v[178:181], v[124:127]
	v_mfma_f32_16x16x32_bf16 v[68:71], v[218:221], v[178:181], v[68:71]
	s_waitcnt lgkmcnt(1)
	v_mfma_f32_16x16x32_bf16 v[128:131], v[158:161], v[222:225], v[128:131]
	v_mfma_f32_16x16x32_bf16 v[132:135], v[162:165], v[222:225], v[132:135]
	v_mfma_f32_16x16x32_bf16 v[136:139], v[214:217], v[222:225], v[136:139]
	v_mfma_f32_16x16x32_bf16 v[84:87], v[218:221], v[222:225], v[84:87]
	s_waitcnt lgkmcnt(0)
	v_mfma_f32_16x16x32_bf16 v[100:103], v[158:161], v[226:229], v[100:103]
	v_mfma_f32_16x16x32_bf16 v[140:143], v[162:165], v[226:229], v[140:143]
	v_mfma_f32_16x16x32_bf16 v[150:153], v[214:217], v[226:229], v[150:153]
	v_mfma_f32_16x16x32_bf16 v[154:157], v[218:221], v[226:229], v[154:157]
	s_add_u32 s64, s0, 0x2000
	s_addc_u32 s65, s1, 0
	s_add_u32 s68, s14, 0x2000
	s_waitcnt vmcnt(0)
	s_barrier
	s_addc_u32 s69, s15, 0
	ds_read_b128 v[158:161], v8
	ds_read_b128 v[162:165], v12
	ds_read_b128 v[166:169], v9
	ds_read_b128 v[178:181], v13
	ds_read_b128 v[214:217], v11
	ds_read_b128 v[218:221], v10
	ds_read_b128 v[222:225], v14
	ds_read_b128 v[226:229], v15
	s_waitcnt lgkmcnt(6)
	v_mfma_f32_16x16x32_bf16 v[40:43], v[158:161], v[162:165], v[40:43]
	s_waitcnt lgkmcnt(5)
	v_mfma_f32_16x16x32_bf16 v[44:47], v[166:169], v[162:165], v[44:47]
	s_waitcnt lgkmcnt(4)
	v_mfma_f32_16x16x32_bf16 v[56:59], v[158:161], v[178:181], v[56:59]
	s_mov_b32 m0, s42
	v_mfma_f32_16x16x32_bf16 v[60:63], v[166:169], v[178:181], v[60:63]
	global_load_lds_dwordx4 v0, s[64:65]
	s_waitcnt lgkmcnt(3)
	v_mfma_f32_16x16x32_bf16 v[48:51], v[214:217], v[162:165], v[48:51]
	v_mfma_f32_16x16x32_bf16 v[64:67], v[214:217], v[178:181], v[64:67]
	s_waitcnt lgkmcnt(2)
	v_mfma_f32_16x16x32_bf16 v[174:177], v[218:221], v[162:165], v[174:177]
	ds_read_b128 v[162:165], v16
	v_mfma_f32_16x16x32_bf16 v[170:173], v[218:221], v[178:181], v[170:173]
	ds_read_b128 v[178:181], v17
	s_waitcnt lgkmcnt(3)
	s_mov_b32 m0, s43
	v_mfma_f32_16x16x32_bf16 v[72:75], v[158:161], v[222:225], v[72:75]
	global_load_lds_dwordx4 v0, s[68:69]
	v_mfma_f32_16x16x32_bf16 v[76:79], v[166:169], v[222:225], v[76:79]
	v_mfma_f32_16x16x32_bf16 v[80:83], v[214:217], v[222:225], v[80:83]
	v_mfma_f32_16x16x32_bf16 v[32:35], v[218:221], v[222:225], v[32:35]
	ds_read_b128 v[222:225], v18
	s_waitcnt lgkmcnt(3)
	v_mfma_f32_16x16x32_bf16 v[88:91], v[158:161], v[226:229], v[88:91]
	s_mov_b32 m0, s44
	v_mfma_f32_16x16x32_bf16 v[92:95], v[166:169], v[226:229], v[92:95]
	global_load_lds_dwordx4 v2, s[64:65]
	v_mfma_f32_16x16x32_bf16 v[96:99], v[214:217], v[226:229], v[96:99]
	v_mfma_f32_16x16x32_bf16 v[36:39], v[218:221], v[226:229], v[36:39]
	ds_read_b128 v[226:229], v19
	s_waitcnt lgkmcnt(3)
	v_mfma_f32_16x16x32_bf16 v[104:107], v[158:161], v[162:165], v[104:107]
	s_waitcnt lgkmcnt(2)
	v_mfma_f32_16x16x32_bf16 v[116:119], v[158:161], v[178:181], v[116:119]
	s_waitcnt lgkmcnt(1)
	s_mov_b32 m0, s45
	v_mfma_f32_16x16x32_bf16 v[128:131], v[158:161], v[222:225], v[128:131]
	global_load_lds_dwordx4 v2, s[68:69]
	s_waitcnt lgkmcnt(0)
	v_mfma_f32_16x16x32_bf16 v[100:103], v[158:161], v[226:229], v[100:103]
	ds_read_b128 v[158:161], v20
	v_mfma_f32_16x16x32_bf16 v[108:111], v[166:169], v[162:165], v[108:111]
	v_mfma_f32_16x16x32_bf16 v[120:123], v[166:169], v[178:181], v[120:123]
	v_mfma_f32_16x16x32_bf16 v[132:135], v[166:169], v[222:225], v[132:135]
	s_mov_b32 m0, s46
	v_mfma_f32_16x16x32_bf16 v[140:143], v[166:169], v[226:229], v[140:143]
	global_load_lds_dwordx4 v4, s[64:65]
	ds_read_b128 v[166:169], v24
	v_mfma_f32_16x16x32_bf16 v[112:115], v[214:217], v[162:165], v[112:115]
	v_mfma_f32_16x16x32_bf16 v[52:55], v[218:221], v[162:165], v[52:55]
	ds_read_b128 v[162:165], v21
	v_mfma_f32_16x16x32_bf16 v[124:127], v[214:217], v[178:181], v[124:127]
	v_mfma_f32_16x16x32_bf16 v[68:71], v[218:221], v[178:181], v[68:71]
	ds_read_b128 v[178:181], v25
	s_mov_b32 m0, s47
	v_mfma_f32_16x16x32_bf16 v[136:139], v[214:217], v[222:225], v[136:139]
	global_load_lds_dwordx4 v4, s[68:69]
	v_mfma_f32_16x16x32_bf16 v[84:87], v[218:221], v[222:225], v[84:87]
	ds_read_b128 v[222:225], v26
	v_mfma_f32_16x16x32_bf16 v[150:153], v[214:217], v[226:229], v[150:153]
	ds_read_b128 v[214:217], v23
	v_mfma_f32_16x16x32_bf16 v[154:157], v[218:221], v[226:229], v[154:157]
	ds_read_b128 v[218:221], v22
	ds_read_b128 v[226:229], v27
	s_waitcnt lgkmcnt(6)
	v_mfma_f32_16x16x32_bf16 v[40:43], v[158:161], v[166:169], v[40:43]
	s_waitcnt lgkmcnt(5)
	s_mov_b32 m0, s49
	v_mfma_f32_16x16x32_bf16 v[44:47], v[162:165], v[166:169], v[44:47]
	global_load_lds_dwordx4 v146, s[64:65]
	s_waitcnt lgkmcnt(4)
	v_mfma_f32_16x16x32_bf16 v[56:59], v[158:161], v[178:181], v[56:59]
	v_mfma_f32_16x16x32_bf16 v[60:63], v[162:165], v[178:181], v[60:63]
	s_waitcnt lgkmcnt(3)
	v_mfma_f32_16x16x32_bf16 v[72:75], v[158:161], v[222:225], v[72:75]
	v_mfma_f32_16x16x32_bf16 v[76:79], v[162:165], v[222:225], v[76:79]
	s_waitcnt lgkmcnt(2)
	s_mov_b32 m0, s50
	v_mfma_f32_16x16x32_bf16 v[48:51], v[214:217], v[166:169], v[48:51]
	global_load_lds_dwordx4 v146, s[68:69]
	s_waitcnt lgkmcnt(1)
	v_mfma_f32_16x16x32_bf16 v[174:177], v[218:221], v[166:169], v[174:177]
	ds_read_b128 v[166:169], v28
	v_mfma_f32_16x16x32_bf16 v[64:67], v[214:217], v[178:181], v[64:67]
	v_mfma_f32_16x16x32_bf16 v[170:173], v[218:221], v[178:181], v[170:173]
	ds_read_b128 v[178:181], v29
	v_mfma_f32_16x16x32_bf16 v[80:83], v[214:217], v[222:225], v[80:83]
	v_mfma_f32_16x16x32_bf16 v[32:35], v[218:221], v[222:225], v[32:35]
	ds_read_b128 v[222:225], v30
	s_waitcnt lgkmcnt(3)
	v_mfma_f32_16x16x32_bf16 v[88:91], v[158:161], v[226:229], v[88:91]
	v_mfma_f32_16x16x32_bf16 v[92:95], v[162:165], v[226:229], v[92:95]
	v_mfma_f32_16x16x32_bf16 v[96:99], v[214:217], v[226:229], v[96:99]
	v_mfma_f32_16x16x32_bf16 v[36:39], v[218:221], v[226:229], v[36:39]
	ds_read_b128 v[226:229], v31
	s_waitcnt lgkmcnt(3)
	v_mfma_f32_16x16x32_bf16 v[104:107], v[158:161], v[166:169], v[104:107]
	v_mfma_f32_16x16x32_bf16 v[108:111], v[162:165], v[166:169], v[108:111]
	v_mfma_f32_16x16x32_bf16 v[112:115], v[214:217], v[166:169], v[112:115]
	v_mfma_f32_16x16x32_bf16 v[52:55], v[218:221], v[166:169], v[52:55]
	s_waitcnt lgkmcnt(2)
	v_mfma_f32_16x16x32_bf16 v[116:119], v[158:161], v[178:181], v[116:119]
	v_mfma_f32_16x16x32_bf16 v[120:123], v[162:165], v[178:181], v[120:123]
	v_mfma_f32_16x16x32_bf16 v[124:127], v[214:217], v[178:181], v[124:127]
	v_mfma_f32_16x16x32_bf16 v[68:71], v[218:221], v[178:181], v[68:71]
	s_waitcnt lgkmcnt(1)
	v_mfma_f32_16x16x32_bf16 v[128:131], v[158:161], v[222:225], v[128:131]
	v_mfma_f32_16x16x32_bf16 v[132:135], v[162:165], v[222:225], v[132:135]
	v_mfma_f32_16x16x32_bf16 v[136:139], v[214:217], v[222:225], v[136:139]
	v_mfma_f32_16x16x32_bf16 v[84:87], v[218:221], v[222:225], v[84:87]
	s_waitcnt lgkmcnt(0)
	v_mfma_f32_16x16x32_bf16 v[100:103], v[158:161], v[226:229], v[100:103]
	v_mfma_f32_16x16x32_bf16 v[140:143], v[162:165], v[226:229], v[140:143]
	v_mfma_f32_16x16x32_bf16 v[150:153], v[214:217], v[226:229], v[150:153]
	v_mfma_f32_16x16x32_bf16 v[154:157], v[218:221], v[226:229], v[154:157]
	s_add_u32 s64, s0, 0x2080
	s_addc_u32 s65, s1, 0
	s_add_u32 s68, s14, 0x2080
	s_waitcnt vmcnt(0)
	s_barrier
	s_addc_u32 s69, s15, 0
	ds_read_b128 v[158:161], v7 offset:32768
	ds_read_b128 v[162:165], v6
	ds_read_b128 v[166:169], v7 offset:34816
	ds_read_b128 v[178:181], v6 offset:2048
	ds_read_b128 v[214:217], v7 offset:36864
	ds_read_b128 v[218:221], v7 offset:38912
	ds_read_b128 v[222:225], v6 offset:4096
	ds_read_b128 v[226:229], v6 offset:6144
	s_waitcnt lgkmcnt(6)
	v_mfma_f32_16x16x32_bf16 v[40:43], v[158:161], v[162:165], v[40:43]
	s_waitcnt lgkmcnt(5)
	v_mfma_f32_16x16x32_bf16 v[44:47], v[166:169], v[162:165], v[44:47]
	s_waitcnt lgkmcnt(4)
	v_mfma_f32_16x16x32_bf16 v[56:59], v[158:161], v[178:181], v[56:59]
	s_mov_b32 m0, s52
	v_mfma_f32_16x16x32_bf16 v[60:63], v[166:169], v[178:181], v[60:63]
	global_load_lds_dwordx4 v0, s[64:65]
	s_waitcnt lgkmcnt(3)
	v_mfma_f32_16x16x32_bf16 v[48:51], v[214:217], v[162:165], v[48:51]
	v_mfma_f32_16x16x32_bf16 v[64:67], v[214:217], v[178:181], v[64:67]
	s_waitcnt lgkmcnt(2)
	v_mfma_f32_16x16x32_bf16 v[174:177], v[218:221], v[162:165], v[174:177]
	ds_read_b128 v[162:165], v6 offset:8192
	v_mfma_f32_16x16x32_bf16 v[170:173], v[218:221], v[178:181], v[170:173]
	ds_read_b128 v[178:181], v6 offset:10240
	s_waitcnt lgkmcnt(3)
	s_mov_b32 m0, s51
	v_mfma_f32_16x16x32_bf16 v[72:75], v[158:161], v[222:225], v[72:75]
	global_load_lds_dwordx4 v0, s[68:69]
	v_mfma_f32_16x16x32_bf16 v[76:79], v[166:169], v[222:225], v[76:79]
	v_mfma_f32_16x16x32_bf16 v[80:83], v[214:217], v[222:225], v[80:83]
	v_mfma_f32_16x16x32_bf16 v[32:35], v[218:221], v[222:225], v[32:35]
	ds_read_b128 v[222:225], v6 offset:12288
	s_waitcnt lgkmcnt(3)
	v_mfma_f32_16x16x32_bf16 v[88:91], v[158:161], v[226:229], v[88:91]
	s_mov_b32 m0, s53
	v_mfma_f32_16x16x32_bf16 v[92:95], v[166:169], v[226:229], v[92:95]
	global_load_lds_dwordx4 v2, s[64:65]
	v_mfma_f32_16x16x32_bf16 v[96:99], v[214:217], v[226:229], v[96:99]
	v_mfma_f32_16x16x32_bf16 v[36:39], v[218:221], v[226:229], v[36:39]
	ds_read_b128 v[226:229], v6 offset:14336
	s_waitcnt lgkmcnt(3)
	v_mfma_f32_16x16x32_bf16 v[104:107], v[158:161], v[162:165], v[104:107]
	s_waitcnt lgkmcnt(2)
	v_mfma_f32_16x16x32_bf16 v[116:119], v[158:161], v[178:181], v[116:119]
	s_waitcnt lgkmcnt(1)
	s_mov_b32 m0, s54
	v_mfma_f32_16x16x32_bf16 v[128:131], v[158:161], v[222:225], v[128:131]
	global_load_lds_dwordx4 v2, s[68:69]
	s_waitcnt lgkmcnt(0)
	v_mfma_f32_16x16x32_bf16 v[100:103], v[158:161], v[226:229], v[100:103]
	ds_read_b128 v[158:161], v7 offset:33792
	v_mfma_f32_16x16x32_bf16 v[108:111], v[166:169], v[162:165], v[108:111]
	v_mfma_f32_16x16x32_bf16 v[120:123], v[166:169], v[178:181], v[120:123]
	v_mfma_f32_16x16x32_bf16 v[132:135], v[166:169], v[222:225], v[132:135]
	s_mov_b32 m0, s55
	v_mfma_f32_16x16x32_bf16 v[140:143], v[166:169], v[226:229], v[140:143]
	global_load_lds_dwordx4 v4, s[64:65]
	ds_read_b128 v[166:169], v6 offset:1024
	v_mfma_f32_16x16x32_bf16 v[112:115], v[214:217], v[162:165], v[112:115]
	v_mfma_f32_16x16x32_bf16 v[52:55], v[218:221], v[162:165], v[52:55]
	ds_read_b128 v[162:165], v7 offset:35840
	v_mfma_f32_16x16x32_bf16 v[124:127], v[214:217], v[178:181], v[124:127]
	v_mfma_f32_16x16x32_bf16 v[68:71], v[218:221], v[178:181], v[68:71]
	ds_read_b128 v[178:181], v6 offset:3072
	s_mov_b32 m0, s58
	v_mfma_f32_16x16x32_bf16 v[136:139], v[214:217], v[222:225], v[136:139]
	global_load_lds_dwordx4 v4, s[68:69]
	v_mfma_f32_16x16x32_bf16 v[84:87], v[218:221], v[222:225], v[84:87]
	ds_read_b128 v[222:225], v6 offset:5120
	v_mfma_f32_16x16x32_bf16 v[150:153], v[214:217], v[226:229], v[150:153]
	ds_read_b128 v[214:217], v7 offset:37888
	v_mfma_f32_16x16x32_bf16 v[154:157], v[218:221], v[226:229], v[154:157]
	ds_read_b128 v[218:221], v7 offset:39936
	ds_read_b128 v[226:229], v6 offset:7168
	s_waitcnt lgkmcnt(6)
	v_mfma_f32_16x16x32_bf16 v[40:43], v[158:161], v[166:169], v[40:43]
	s_waitcnt lgkmcnt(5)
	s_mov_b32 m0, s62
	v_mfma_f32_16x16x32_bf16 v[44:47], v[162:165], v[166:169], v[44:47]
	global_load_lds_dwordx4 v146, s[64:65]
	s_waitcnt lgkmcnt(4)
	v_mfma_f32_16x16x32_bf16 v[56:59], v[158:161], v[178:181], v[56:59]
	v_mfma_f32_16x16x32_bf16 v[60:63], v[162:165], v[178:181], v[60:63]
	s_waitcnt lgkmcnt(3)
	v_mfma_f32_16x16x32_bf16 v[72:75], v[158:161], v[222:225], v[72:75]
	v_mfma_f32_16x16x32_bf16 v[76:79], v[162:165], v[222:225], v[76:79]
	s_waitcnt lgkmcnt(2)
	s_mov_b32 m0, s63
	v_mfma_f32_16x16x32_bf16 v[48:51], v[214:217], v[166:169], v[48:51]
	global_load_lds_dwordx4 v146, s[68:69]
	s_waitcnt lgkmcnt(1)
	v_mfma_f32_16x16x32_bf16 v[174:177], v[218:221], v[166:169], v[174:177]
	ds_read_b128 v[166:169], v6 offset:9216
	v_mfma_f32_16x16x32_bf16 v[64:67], v[214:217], v[178:181], v[64:67]
	v_mfma_f32_16x16x32_bf16 v[170:173], v[218:221], v[178:181], v[170:173]
	ds_read_b128 v[178:181], v6 offset:11264
	v_mfma_f32_16x16x32_bf16 v[80:83], v[214:217], v[222:225], v[80:83]
	v_mfma_f32_16x16x32_bf16 v[32:35], v[218:221], v[222:225], v[32:35]
	ds_read_b128 v[222:225], v6 offset:13312
	s_waitcnt lgkmcnt(3)
	v_mfma_f32_16x16x32_bf16 v[88:91], v[158:161], v[226:229], v[88:91]
	v_mfma_f32_16x16x32_bf16 v[92:95], v[162:165], v[226:229], v[92:95]
	v_mfma_f32_16x16x32_bf16 v[96:99], v[214:217], v[226:229], v[96:99]
	v_mfma_f32_16x16x32_bf16 v[36:39], v[218:221], v[226:229], v[36:39]
	ds_read_b128 v[226:229], v6 offset:15360
	s_waitcnt lgkmcnt(3)
	v_mfma_f32_16x16x32_bf16 v[104:107], v[158:161], v[166:169], v[104:107]
	v_mfma_f32_16x16x32_bf16 v[108:111], v[162:165], v[166:169], v[108:111]
	v_mfma_f32_16x16x32_bf16 v[112:115], v[214:217], v[166:169], v[112:115]
	v_mfma_f32_16x16x32_bf16 v[52:55], v[218:221], v[166:169], v[52:55]
	s_waitcnt lgkmcnt(2)
	v_mfma_f32_16x16x32_bf16 v[116:119], v[158:161], v[178:181], v[116:119]
	v_mfma_f32_16x16x32_bf16 v[120:123], v[162:165], v[178:181], v[120:123]
	v_mfma_f32_16x16x32_bf16 v[124:127], v[214:217], v[178:181], v[124:127]
	v_mfma_f32_16x16x32_bf16 v[68:71], v[218:221], v[178:181], v[68:71]
	s_waitcnt lgkmcnt(1)
	v_mfma_f32_16x16x32_bf16 v[128:131], v[158:161], v[222:225], v[128:131]
	v_mfma_f32_16x16x32_bf16 v[132:135], v[162:165], v[222:225], v[132:135]
	v_mfma_f32_16x16x32_bf16 v[136:139], v[214:217], v[222:225], v[136:139]
	v_mfma_f32_16x16x32_bf16 v[84:87], v[218:221], v[222:225], v[84:87]
	s_waitcnt lgkmcnt(0)
	v_mfma_f32_16x16x32_bf16 v[100:103], v[158:161], v[226:229], v[100:103]
	v_mfma_f32_16x16x32_bf16 v[140:143], v[162:165], v[226:229], v[140:143]
	v_mfma_f32_16x16x32_bf16 v[150:153], v[214:217], v[226:229], v[150:153]
	v_mfma_f32_16x16x32_bf16 v[154:157], v[218:221], v[226:229], v[154:157]
	s_add_u32 s64, s0, 0x2100
	s_addc_u32 s65, s1, 0
	s_add_u32 s68, s14, 0x2100
	s_waitcnt vmcnt(0)
	s_barrier
	s_addc_u32 s69, s15, 0
	ds_read_b128 v[158:161], v8
	ds_read_b128 v[162:165], v12
	ds_read_b128 v[166:169], v9
	ds_read_b128 v[178:181], v13
	ds_read_b128 v[214:217], v11
	ds_read_b128 v[218:221], v10
	ds_read_b128 v[222:225], v14
	ds_read_b128 v[226:229], v15
	s_waitcnt lgkmcnt(6)
	v_mfma_f32_16x16x32_bf16 v[40:43], v[158:161], v[162:165], v[40:43]
	s_waitcnt lgkmcnt(5)
	v_mfma_f32_16x16x32_bf16 v[44:47], v[166:169], v[162:165], v[44:47]
	s_waitcnt lgkmcnt(4)
	v_mfma_f32_16x16x32_bf16 v[56:59], v[158:161], v[178:181], v[56:59]
	s_mov_b32 m0, s42
	v_mfma_f32_16x16x32_bf16 v[60:63], v[166:169], v[178:181], v[60:63]
	global_load_lds_dwordx4 v0, s[64:65]
	s_waitcnt lgkmcnt(3)
	v_mfma_f32_16x16x32_bf16 v[48:51], v[214:217], v[162:165], v[48:51]
	v_mfma_f32_16x16x32_bf16 v[64:67], v[214:217], v[178:181], v[64:67]
	s_waitcnt lgkmcnt(2)
	v_mfma_f32_16x16x32_bf16 v[174:177], v[218:221], v[162:165], v[174:177]
	ds_read_b128 v[162:165], v16
	v_mfma_f32_16x16x32_bf16 v[170:173], v[218:221], v[178:181], v[170:173]
	ds_read_b128 v[178:181], v17
	s_waitcnt lgkmcnt(3)
	s_mov_b32 m0, s43
	v_mfma_f32_16x16x32_bf16 v[72:75], v[158:161], v[222:225], v[72:75]
	global_load_lds_dwordx4 v0, s[68:69]
	v_mfma_f32_16x16x32_bf16 v[76:79], v[166:169], v[222:225], v[76:79]
	v_mfma_f32_16x16x32_bf16 v[80:83], v[214:217], v[222:225], v[80:83]
	v_mfma_f32_16x16x32_bf16 v[32:35], v[218:221], v[222:225], v[32:35]
	ds_read_b128 v[222:225], v18
	s_waitcnt lgkmcnt(3)
	v_mfma_f32_16x16x32_bf16 v[88:91], v[158:161], v[226:229], v[88:91]
	s_mov_b32 m0, s44
	v_mfma_f32_16x16x32_bf16 v[92:95], v[166:169], v[226:229], v[92:95]
	global_load_lds_dwordx4 v2, s[64:65]
	v_mfma_f32_16x16x32_bf16 v[96:99], v[214:217], v[226:229], v[96:99]
	v_mfma_f32_16x16x32_bf16 v[36:39], v[218:221], v[226:229], v[36:39]
	ds_read_b128 v[226:229], v19
	s_waitcnt lgkmcnt(3)
	v_mfma_f32_16x16x32_bf16 v[104:107], v[158:161], v[162:165], v[104:107]
	s_waitcnt lgkmcnt(2)
	v_mfma_f32_16x16x32_bf16 v[116:119], v[158:161], v[178:181], v[116:119]
	s_waitcnt lgkmcnt(1)
	s_mov_b32 m0, s45
	v_mfma_f32_16x16x32_bf16 v[128:131], v[158:161], v[222:225], v[128:131]
	global_load_lds_dwordx4 v2, s[68:69]
	s_waitcnt lgkmcnt(0)
	v_mfma_f32_16x16x32_bf16 v[100:103], v[158:161], v[226:229], v[100:103]
	ds_read_b128 v[158:161], v20
	v_mfma_f32_16x16x32_bf16 v[108:111], v[166:169], v[162:165], v[108:111]
	v_mfma_f32_16x16x32_bf16 v[120:123], v[166:169], v[178:181], v[120:123]
	v_mfma_f32_16x16x32_bf16 v[132:135], v[166:169], v[222:225], v[132:135]
	s_mov_b32 m0, s46
	v_mfma_f32_16x16x32_bf16 v[140:143], v[166:169], v[226:229], v[140:143]
	global_load_lds_dwordx4 v4, s[64:65]
	ds_read_b128 v[166:169], v24
	v_mfma_f32_16x16x32_bf16 v[112:115], v[214:217], v[162:165], v[112:115]
	v_mfma_f32_16x16x32_bf16 v[52:55], v[218:221], v[162:165], v[52:55]
	ds_read_b128 v[162:165], v21
	v_mfma_f32_16x16x32_bf16 v[124:127], v[214:217], v[178:181], v[124:127]
	v_mfma_f32_16x16x32_bf16 v[68:71], v[218:221], v[178:181], v[68:71]
	ds_read_b128 v[178:181], v25
	s_mov_b32 m0, s47
	v_mfma_f32_16x16x32_bf16 v[136:139], v[214:217], v[222:225], v[136:139]
	global_load_lds_dwordx4 v4, s[68:69]
	v_mfma_f32_16x16x32_bf16 v[84:87], v[218:221], v[222:225], v[84:87]
	ds_read_b128 v[222:225], v26
	v_mfma_f32_16x16x32_bf16 v[150:153], v[214:217], v[226:229], v[150:153]
	ds_read_b128 v[214:217], v23
	v_mfma_f32_16x16x32_bf16 v[154:157], v[218:221], v[226:229], v[154:157]
	ds_read_b128 v[218:221], v22
	ds_read_b128 v[226:229], v27
	s_waitcnt lgkmcnt(6)
	v_mfma_f32_16x16x32_bf16 v[40:43], v[158:161], v[166:169], v[40:43]
	s_waitcnt lgkmcnt(5)
	s_mov_b32 m0, s49
	v_mfma_f32_16x16x32_bf16 v[44:47], v[162:165], v[166:169], v[44:47]
	global_load_lds_dwordx4 v146, s[64:65]
	s_waitcnt lgkmcnt(4)
	v_mfma_f32_16x16x32_bf16 v[56:59], v[158:161], v[178:181], v[56:59]
	v_mfma_f32_16x16x32_bf16 v[60:63], v[162:165], v[178:181], v[60:63]
	s_waitcnt lgkmcnt(3)
	v_mfma_f32_16x16x32_bf16 v[72:75], v[158:161], v[222:225], v[72:75]
	v_mfma_f32_16x16x32_bf16 v[76:79], v[162:165], v[222:225], v[76:79]
	s_waitcnt lgkmcnt(2)
	s_mov_b32 m0, s50
	v_mfma_f32_16x16x32_bf16 v[48:51], v[214:217], v[166:169], v[48:51]
	global_load_lds_dwordx4 v146, s[68:69]
	s_waitcnt lgkmcnt(1)
	v_mfma_f32_16x16x32_bf16 v[174:177], v[218:221], v[166:169], v[174:177]
	ds_read_b128 v[166:169], v28
	v_mfma_f32_16x16x32_bf16 v[64:67], v[214:217], v[178:181], v[64:67]
	v_mfma_f32_16x16x32_bf16 v[170:173], v[218:221], v[178:181], v[170:173]
	ds_read_b128 v[178:181], v29
	v_mfma_f32_16x16x32_bf16 v[80:83], v[214:217], v[222:225], v[80:83]
	v_mfma_f32_16x16x32_bf16 v[32:35], v[218:221], v[222:225], v[32:35]
	ds_read_b128 v[222:225], v30
	s_waitcnt lgkmcnt(3)
	v_mfma_f32_16x16x32_bf16 v[88:91], v[158:161], v[226:229], v[88:91]
	v_mfma_f32_16x16x32_bf16 v[92:95], v[162:165], v[226:229], v[92:95]
	v_mfma_f32_16x16x32_bf16 v[96:99], v[214:217], v[226:229], v[96:99]
	v_mfma_f32_16x16x32_bf16 v[36:39], v[218:221], v[226:229], v[36:39]
	ds_read_b128 v[226:229], v31
	s_waitcnt lgkmcnt(3)
	v_mfma_f32_16x16x32_bf16 v[104:107], v[158:161], v[166:169], v[104:107]
	v_mfma_f32_16x16x32_bf16 v[108:111], v[162:165], v[166:169], v[108:111]
	v_mfma_f32_16x16x32_bf16 v[112:115], v[214:217], v[166:169], v[112:115]
	v_mfma_f32_16x16x32_bf16 v[52:55], v[218:221], v[166:169], v[52:55]
	s_waitcnt lgkmcnt(2)
	v_mfma_f32_16x16x32_bf16 v[116:119], v[158:161], v[178:181], v[116:119]
	v_mfma_f32_16x16x32_bf16 v[120:123], v[162:165], v[178:181], v[120:123]
	v_mfma_f32_16x16x32_bf16 v[124:127], v[214:217], v[178:181], v[124:127]
	v_mfma_f32_16x16x32_bf16 v[68:71], v[218:221], v[178:181], v[68:71]
	s_waitcnt lgkmcnt(1)
	v_mfma_f32_16x16x32_bf16 v[128:131], v[158:161], v[222:225], v[128:131]
	v_mfma_f32_16x16x32_bf16 v[132:135], v[162:165], v[222:225], v[132:135]
	v_mfma_f32_16x16x32_bf16 v[136:139], v[214:217], v[222:225], v[136:139]
	v_mfma_f32_16x16x32_bf16 v[84:87], v[218:221], v[222:225], v[84:87]
	s_waitcnt lgkmcnt(0)
	v_mfma_f32_16x16x32_bf16 v[100:103], v[158:161], v[226:229], v[100:103]
	v_mfma_f32_16x16x32_bf16 v[140:143], v[162:165], v[226:229], v[140:143]
	v_mfma_f32_16x16x32_bf16 v[150:153], v[214:217], v[226:229], v[150:153]
	v_mfma_f32_16x16x32_bf16 v[154:157], v[218:221], v[226:229], v[154:157]
	s_add_u32 s64, s0, 0x2180
	s_addc_u32 s65, s1, 0
	s_add_u32 s68, s14, 0x2180
	s_waitcnt vmcnt(0)
	s_barrier
	s_addc_u32 s69, s15, 0
	ds_read_b128 v[158:161], v7 offset:32768
	ds_read_b128 v[162:165], v6
	ds_read_b128 v[166:169], v7 offset:34816
	ds_read_b128 v[178:181], v6 offset:2048
	ds_read_b128 v[214:217], v7 offset:36864
	ds_read_b128 v[218:221], v7 offset:38912
	ds_read_b128 v[222:225], v6 offset:4096
	ds_read_b128 v[226:229], v6 offset:6144
	s_waitcnt lgkmcnt(6)
	v_mfma_f32_16x16x32_bf16 v[40:43], v[158:161], v[162:165], v[40:43]
	s_waitcnt lgkmcnt(5)
	v_mfma_f32_16x16x32_bf16 v[44:47], v[166:169], v[162:165], v[44:47]
	s_waitcnt lgkmcnt(4)
	v_mfma_f32_16x16x32_bf16 v[56:59], v[158:161], v[178:181], v[56:59]
	s_mov_b32 m0, s52
	v_mfma_f32_16x16x32_bf16 v[60:63], v[166:169], v[178:181], v[60:63]
	global_load_lds_dwordx4 v0, s[64:65]
	s_waitcnt lgkmcnt(3)
	v_mfma_f32_16x16x32_bf16 v[48:51], v[214:217], v[162:165], v[48:51]
	v_mfma_f32_16x16x32_bf16 v[64:67], v[214:217], v[178:181], v[64:67]
	s_waitcnt lgkmcnt(2)
	v_mfma_f32_16x16x32_bf16 v[174:177], v[218:221], v[162:165], v[174:177]
	ds_read_b128 v[162:165], v6 offset:8192
	v_mfma_f32_16x16x32_bf16 v[170:173], v[218:221], v[178:181], v[170:173]
	ds_read_b128 v[178:181], v6 offset:10240
	s_waitcnt lgkmcnt(3)
	s_mov_b32 m0, s51
	v_mfma_f32_16x16x32_bf16 v[72:75], v[158:161], v[222:225], v[72:75]
	global_load_lds_dwordx4 v0, s[68:69]
	v_mfma_f32_16x16x32_bf16 v[76:79], v[166:169], v[222:225], v[76:79]
	v_mfma_f32_16x16x32_bf16 v[80:83], v[214:217], v[222:225], v[80:83]
	v_mfma_f32_16x16x32_bf16 v[32:35], v[218:221], v[222:225], v[32:35]
	ds_read_b128 v[222:225], v6 offset:12288
	s_waitcnt lgkmcnt(3)
	v_mfma_f32_16x16x32_bf16 v[88:91], v[158:161], v[226:229], v[88:91]
	s_mov_b32 m0, s53
	v_mfma_f32_16x16x32_bf16 v[92:95], v[166:169], v[226:229], v[92:95]
	global_load_lds_dwordx4 v2, s[64:65]
	v_mfma_f32_16x16x32_bf16 v[96:99], v[214:217], v[226:229], v[96:99]
	v_mfma_f32_16x16x32_bf16 v[36:39], v[218:221], v[226:229], v[36:39]
	ds_read_b128 v[226:229], v6 offset:14336
	s_waitcnt lgkmcnt(3)
	v_mfma_f32_16x16x32_bf16 v[104:107], v[158:161], v[162:165], v[104:107]
	s_waitcnt lgkmcnt(2)
	v_mfma_f32_16x16x32_bf16 v[116:119], v[158:161], v[178:181], v[116:119]
	s_waitcnt lgkmcnt(1)
	s_mov_b32 m0, s54
	v_mfma_f32_16x16x32_bf16 v[128:131], v[158:161], v[222:225], v[128:131]
	global_load_lds_dwordx4 v2, s[68:69]
	s_waitcnt lgkmcnt(0)
	v_mfma_f32_16x16x32_bf16 v[100:103], v[158:161], v[226:229], v[100:103]
	ds_read_b128 v[158:161], v7 offset:33792
	v_mfma_f32_16x16x32_bf16 v[108:111], v[166:169], v[162:165], v[108:111]
	v_mfma_f32_16x16x32_bf16 v[120:123], v[166:169], v[178:181], v[120:123]
	v_mfma_f32_16x16x32_bf16 v[132:135], v[166:169], v[222:225], v[132:135]
	s_mov_b32 m0, s55
	v_mfma_f32_16x16x32_bf16 v[140:143], v[166:169], v[226:229], v[140:143]
	global_load_lds_dwordx4 v4, s[64:65]
	ds_read_b128 v[166:169], v6 offset:1024
	v_mfma_f32_16x16x32_bf16 v[112:115], v[214:217], v[162:165], v[112:115]
	v_mfma_f32_16x16x32_bf16 v[52:55], v[218:221], v[162:165], v[52:55]
	ds_read_b128 v[162:165], v7 offset:35840
	v_mfma_f32_16x16x32_bf16 v[124:127], v[214:217], v[178:181], v[124:127]
	v_mfma_f32_16x16x32_bf16 v[68:71], v[218:221], v[178:181], v[68:71]
	ds_read_b128 v[178:181], v6 offset:3072
	s_mov_b32 m0, s58
	v_mfma_f32_16x16x32_bf16 v[136:139], v[214:217], v[222:225], v[136:139]
	global_load_lds_dwordx4 v4, s[68:69]
	v_mfma_f32_16x16x32_bf16 v[84:87], v[218:221], v[222:225], v[84:87]
	ds_read_b128 v[222:225], v6 offset:5120
	v_mfma_f32_16x16x32_bf16 v[150:153], v[214:217], v[226:229], v[150:153]
	ds_read_b128 v[214:217], v7 offset:37888
	v_mfma_f32_16x16x32_bf16 v[154:157], v[218:221], v[226:229], v[154:157]
	ds_read_b128 v[218:221], v7 offset:39936
	ds_read_b128 v[226:229], v6 offset:7168
	s_waitcnt lgkmcnt(6)
	v_mfma_f32_16x16x32_bf16 v[40:43], v[158:161], v[166:169], v[40:43]
	s_waitcnt lgkmcnt(5)
	s_mov_b32 m0, s62
	v_mfma_f32_16x16x32_bf16 v[44:47], v[162:165], v[166:169], v[44:47]
	global_load_lds_dwordx4 v146, s[64:65]
	s_waitcnt lgkmcnt(4)
	v_mfma_f32_16x16x32_bf16 v[56:59], v[158:161], v[178:181], v[56:59]
	v_mfma_f32_16x16x32_bf16 v[60:63], v[162:165], v[178:181], v[60:63]
	s_waitcnt lgkmcnt(3)
	v_mfma_f32_16x16x32_bf16 v[72:75], v[158:161], v[222:225], v[72:75]
	v_mfma_f32_16x16x32_bf16 v[76:79], v[162:165], v[222:225], v[76:79]
	s_waitcnt lgkmcnt(2)
	s_mov_b32 m0, s63
	v_mfma_f32_16x16x32_bf16 v[48:51], v[214:217], v[166:169], v[48:51]
	global_load_lds_dwordx4 v146, s[68:69]
	s_waitcnt lgkmcnt(1)
	v_mfma_f32_16x16x32_bf16 v[174:177], v[218:221], v[166:169], v[174:177]
	ds_read_b128 v[166:169], v6 offset:9216
	v_mfma_f32_16x16x32_bf16 v[64:67], v[214:217], v[178:181], v[64:67]
	v_mfma_f32_16x16x32_bf16 v[170:173], v[218:221], v[178:181], v[170:173]
	ds_read_b128 v[178:181], v6 offset:11264
	v_mfma_f32_16x16x32_bf16 v[80:83], v[214:217], v[222:225], v[80:83]
	v_mfma_f32_16x16x32_bf16 v[32:35], v[218:221], v[222:225], v[32:35]
	ds_read_b128 v[222:225], v6 offset:13312
	s_waitcnt lgkmcnt(3)
	v_mfma_f32_16x16x32_bf16 v[88:91], v[158:161], v[226:229], v[88:91]
	v_mfma_f32_16x16x32_bf16 v[92:95], v[162:165], v[226:229], v[92:95]
	v_mfma_f32_16x16x32_bf16 v[96:99], v[214:217], v[226:229], v[96:99]
	v_mfma_f32_16x16x32_bf16 v[36:39], v[218:221], v[226:229], v[36:39]
	ds_read_b128 v[226:229], v6 offset:15360
	s_waitcnt lgkmcnt(3)
	v_mfma_f32_16x16x32_bf16 v[104:107], v[158:161], v[166:169], v[104:107]
	v_mfma_f32_16x16x32_bf16 v[108:111], v[162:165], v[166:169], v[108:111]
	v_mfma_f32_16x16x32_bf16 v[112:115], v[214:217], v[166:169], v[112:115]
	v_mfma_f32_16x16x32_bf16 v[52:55], v[218:221], v[166:169], v[52:55]
	s_waitcnt lgkmcnt(2)
	v_mfma_f32_16x16x32_bf16 v[116:119], v[158:161], v[178:181], v[116:119]
	v_mfma_f32_16x16x32_bf16 v[120:123], v[162:165], v[178:181], v[120:123]
	v_mfma_f32_16x16x32_bf16 v[124:127], v[214:217], v[178:181], v[124:127]
	v_mfma_f32_16x16x32_bf16 v[68:71], v[218:221], v[178:181], v[68:71]
	s_waitcnt lgkmcnt(1)
	v_mfma_f32_16x16x32_bf16 v[128:131], v[158:161], v[222:225], v[128:131]
	v_mfma_f32_16x16x32_bf16 v[132:135], v[162:165], v[222:225], v[132:135]
	v_mfma_f32_16x16x32_bf16 v[136:139], v[214:217], v[222:225], v[136:139]
	v_mfma_f32_16x16x32_bf16 v[84:87], v[218:221], v[222:225], v[84:87]
	s_waitcnt lgkmcnt(0)
	v_mfma_f32_16x16x32_bf16 v[100:103], v[158:161], v[226:229], v[100:103]
	v_mfma_f32_16x16x32_bf16 v[140:143], v[162:165], v[226:229], v[140:143]
	v_mfma_f32_16x16x32_bf16 v[150:153], v[214:217], v[226:229], v[150:153]
	v_mfma_f32_16x16x32_bf16 v[154:157], v[218:221], v[226:229], v[154:157]
	s_add_u32 s64, s0, 0x2200
	s_addc_u32 s65, s1, 0
	s_add_u32 s68, s14, 0x2200
	s_waitcnt vmcnt(0)
	s_barrier
	s_addc_u32 s69, s15, 0
	ds_read_b128 v[158:161], v8
	ds_read_b128 v[162:165], v12
	ds_read_b128 v[166:169], v9
	ds_read_b128 v[178:181], v13
	ds_read_b128 v[214:217], v11
	ds_read_b128 v[218:221], v10
	ds_read_b128 v[222:225], v14
	ds_read_b128 v[226:229], v15
	s_waitcnt lgkmcnt(6)
	v_mfma_f32_16x16x32_bf16 v[40:43], v[158:161], v[162:165], v[40:43]
	s_waitcnt lgkmcnt(5)
	v_mfma_f32_16x16x32_bf16 v[44:47], v[166:169], v[162:165], v[44:47]
	s_waitcnt lgkmcnt(4)
	v_mfma_f32_16x16x32_bf16 v[56:59], v[158:161], v[178:181], v[56:59]
	s_mov_b32 m0, s42
	v_mfma_f32_16x16x32_bf16 v[60:63], v[166:169], v[178:181], v[60:63]
	global_load_lds_dwordx4 v0, s[64:65]
	s_waitcnt lgkmcnt(3)
	v_mfma_f32_16x16x32_bf16 v[48:51], v[214:217], v[162:165], v[48:51]
	v_mfma_f32_16x16x32_bf16 v[64:67], v[214:217], v[178:181], v[64:67]
	s_waitcnt lgkmcnt(2)
	v_mfma_f32_16x16x32_bf16 v[174:177], v[218:221], v[162:165], v[174:177]
	ds_read_b128 v[162:165], v16
	v_mfma_f32_16x16x32_bf16 v[170:173], v[218:221], v[178:181], v[170:173]
	ds_read_b128 v[178:181], v17
	s_waitcnt lgkmcnt(3)
	s_mov_b32 m0, s43
	v_mfma_f32_16x16x32_bf16 v[72:75], v[158:161], v[222:225], v[72:75]
	global_load_lds_dwordx4 v0, s[68:69]
	v_mfma_f32_16x16x32_bf16 v[76:79], v[166:169], v[222:225], v[76:79]
	v_mfma_f32_16x16x32_bf16 v[80:83], v[214:217], v[222:225], v[80:83]
	v_mfma_f32_16x16x32_bf16 v[32:35], v[218:221], v[222:225], v[32:35]
	ds_read_b128 v[222:225], v18
	s_waitcnt lgkmcnt(3)
	v_mfma_f32_16x16x32_bf16 v[88:91], v[158:161], v[226:229], v[88:91]
	s_mov_b32 m0, s44
	v_mfma_f32_16x16x32_bf16 v[92:95], v[166:169], v[226:229], v[92:95]
	global_load_lds_dwordx4 v2, s[64:65]
	v_mfma_f32_16x16x32_bf16 v[96:99], v[214:217], v[226:229], v[96:99]
	v_mfma_f32_16x16x32_bf16 v[36:39], v[218:221], v[226:229], v[36:39]
	ds_read_b128 v[226:229], v19
	s_waitcnt lgkmcnt(3)
	v_mfma_f32_16x16x32_bf16 v[104:107], v[158:161], v[162:165], v[104:107]
	s_waitcnt lgkmcnt(2)
	v_mfma_f32_16x16x32_bf16 v[116:119], v[158:161], v[178:181], v[116:119]
	s_waitcnt lgkmcnt(1)
	s_mov_b32 m0, s45
	v_mfma_f32_16x16x32_bf16 v[128:131], v[158:161], v[222:225], v[128:131]
	global_load_lds_dwordx4 v2, s[68:69]
	s_waitcnt lgkmcnt(0)
	v_mfma_f32_16x16x32_bf16 v[100:103], v[158:161], v[226:229], v[100:103]
	ds_read_b128 v[158:161], v20
	v_mfma_f32_16x16x32_bf16 v[108:111], v[166:169], v[162:165], v[108:111]
	v_mfma_f32_16x16x32_bf16 v[120:123], v[166:169], v[178:181], v[120:123]
	v_mfma_f32_16x16x32_bf16 v[132:135], v[166:169], v[222:225], v[132:135]
	s_mov_b32 m0, s46
	v_mfma_f32_16x16x32_bf16 v[140:143], v[166:169], v[226:229], v[140:143]
	global_load_lds_dwordx4 v4, s[64:65]
	ds_read_b128 v[166:169], v24
	v_mfma_f32_16x16x32_bf16 v[112:115], v[214:217], v[162:165], v[112:115]
	v_mfma_f32_16x16x32_bf16 v[52:55], v[218:221], v[162:165], v[52:55]
	ds_read_b128 v[162:165], v21
	v_mfma_f32_16x16x32_bf16 v[124:127], v[214:217], v[178:181], v[124:127]
	v_mfma_f32_16x16x32_bf16 v[68:71], v[218:221], v[178:181], v[68:71]
	ds_read_b128 v[178:181], v25
	s_mov_b32 m0, s47
	v_mfma_f32_16x16x32_bf16 v[136:139], v[214:217], v[222:225], v[136:139]
	global_load_lds_dwordx4 v4, s[68:69]
	v_mfma_f32_16x16x32_bf16 v[84:87], v[218:221], v[222:225], v[84:87]
	ds_read_b128 v[222:225], v26
	v_mfma_f32_16x16x32_bf16 v[150:153], v[214:217], v[226:229], v[150:153]
	ds_read_b128 v[214:217], v23
	v_mfma_f32_16x16x32_bf16 v[154:157], v[218:221], v[226:229], v[154:157]
	ds_read_b128 v[218:221], v22
	ds_read_b128 v[226:229], v27
	s_waitcnt lgkmcnt(6)
	v_mfma_f32_16x16x32_bf16 v[40:43], v[158:161], v[166:169], v[40:43]
	s_waitcnt lgkmcnt(5)
	s_mov_b32 m0, s49
	v_mfma_f32_16x16x32_bf16 v[44:47], v[162:165], v[166:169], v[44:47]
	global_load_lds_dwordx4 v146, s[64:65]
	s_waitcnt lgkmcnt(4)
	v_mfma_f32_16x16x32_bf16 v[56:59], v[158:161], v[178:181], v[56:59]
	v_mfma_f32_16x16x32_bf16 v[60:63], v[162:165], v[178:181], v[60:63]
	s_waitcnt lgkmcnt(3)
	v_mfma_f32_16x16x32_bf16 v[72:75], v[158:161], v[222:225], v[72:75]
	v_mfma_f32_16x16x32_bf16 v[76:79], v[162:165], v[222:225], v[76:79]
	s_waitcnt lgkmcnt(2)
	s_mov_b32 m0, s50
	v_mfma_f32_16x16x32_bf16 v[48:51], v[214:217], v[166:169], v[48:51]
	global_load_lds_dwordx4 v146, s[68:69]
	s_waitcnt lgkmcnt(1)
	v_mfma_f32_16x16x32_bf16 v[174:177], v[218:221], v[166:169], v[174:177]
	ds_read_b128 v[166:169], v28
	v_mfma_f32_16x16x32_bf16 v[64:67], v[214:217], v[178:181], v[64:67]
	v_mfma_f32_16x16x32_bf16 v[170:173], v[218:221], v[178:181], v[170:173]
	ds_read_b128 v[178:181], v29
	v_mfma_f32_16x16x32_bf16 v[80:83], v[214:217], v[222:225], v[80:83]
	v_mfma_f32_16x16x32_bf16 v[32:35], v[218:221], v[222:225], v[32:35]
	ds_read_b128 v[222:225], v30
	s_waitcnt lgkmcnt(3)
	v_mfma_f32_16x16x32_bf16 v[88:91], v[158:161], v[226:229], v[88:91]
	v_mfma_f32_16x16x32_bf16 v[92:95], v[162:165], v[226:229], v[92:95]
	v_mfma_f32_16x16x32_bf16 v[96:99], v[214:217], v[226:229], v[96:99]
	v_mfma_f32_16x16x32_bf16 v[36:39], v[218:221], v[226:229], v[36:39]
	ds_read_b128 v[226:229], v31
	s_waitcnt lgkmcnt(3)
	v_mfma_f32_16x16x32_bf16 v[104:107], v[158:161], v[166:169], v[104:107]
	v_mfma_f32_16x16x32_bf16 v[108:111], v[162:165], v[166:169], v[108:111]
	v_mfma_f32_16x16x32_bf16 v[112:115], v[214:217], v[166:169], v[112:115]
	v_mfma_f32_16x16x32_bf16 v[52:55], v[218:221], v[166:169], v[52:55]
	s_waitcnt lgkmcnt(2)
	v_mfma_f32_16x16x32_bf16 v[116:119], v[158:161], v[178:181], v[116:119]
	v_mfma_f32_16x16x32_bf16 v[120:123], v[162:165], v[178:181], v[120:123]
	v_mfma_f32_16x16x32_bf16 v[124:127], v[214:217], v[178:181], v[124:127]
	v_mfma_f32_16x16x32_bf16 v[68:71], v[218:221], v[178:181], v[68:71]
	s_waitcnt lgkmcnt(1)
	v_mfma_f32_16x16x32_bf16 v[128:131], v[158:161], v[222:225], v[128:131]
	v_mfma_f32_16x16x32_bf16 v[132:135], v[162:165], v[222:225], v[132:135]
	v_mfma_f32_16x16x32_bf16 v[136:139], v[214:217], v[222:225], v[136:139]
	v_mfma_f32_16x16x32_bf16 v[84:87], v[218:221], v[222:225], v[84:87]
	s_waitcnt lgkmcnt(0)
	v_mfma_f32_16x16x32_bf16 v[100:103], v[158:161], v[226:229], v[100:103]
	v_mfma_f32_16x16x32_bf16 v[140:143], v[162:165], v[226:229], v[140:143]
	v_mfma_f32_16x16x32_bf16 v[150:153], v[214:217], v[226:229], v[150:153]
	v_mfma_f32_16x16x32_bf16 v[154:157], v[218:221], v[226:229], v[154:157]
	s_add_u32 s64, s0, 0x2280
	s_addc_u32 s65, s1, 0
	s_add_u32 s68, s14, 0x2280
	s_waitcnt vmcnt(0)
	s_barrier
	s_addc_u32 s69, s15, 0
	ds_read_b128 v[158:161], v7 offset:32768
	ds_read_b128 v[162:165], v6
	ds_read_b128 v[166:169], v7 offset:34816
	ds_read_b128 v[178:181], v6 offset:2048
	ds_read_b128 v[214:217], v7 offset:36864
	ds_read_b128 v[218:221], v7 offset:38912
	ds_read_b128 v[222:225], v6 offset:4096
	ds_read_b128 v[226:229], v6 offset:6144
	s_waitcnt lgkmcnt(6)
	v_mfma_f32_16x16x32_bf16 v[40:43], v[158:161], v[162:165], v[40:43]
	s_waitcnt lgkmcnt(5)
	v_mfma_f32_16x16x32_bf16 v[44:47], v[166:169], v[162:165], v[44:47]
	s_waitcnt lgkmcnt(4)
	v_mfma_f32_16x16x32_bf16 v[56:59], v[158:161], v[178:181], v[56:59]
	s_mov_b32 m0, s52
	v_mfma_f32_16x16x32_bf16 v[60:63], v[166:169], v[178:181], v[60:63]
	global_load_lds_dwordx4 v0, s[64:65]
	s_waitcnt lgkmcnt(3)
	v_mfma_f32_16x16x32_bf16 v[48:51], v[214:217], v[162:165], v[48:51]
	v_mfma_f32_16x16x32_bf16 v[64:67], v[214:217], v[178:181], v[64:67]
	s_waitcnt lgkmcnt(2)
	v_mfma_f32_16x16x32_bf16 v[174:177], v[218:221], v[162:165], v[174:177]
	ds_read_b128 v[162:165], v6 offset:8192
	v_mfma_f32_16x16x32_bf16 v[170:173], v[218:221], v[178:181], v[170:173]
	ds_read_b128 v[178:181], v6 offset:10240
	s_waitcnt lgkmcnt(3)
	s_mov_b32 m0, s51
	v_mfma_f32_16x16x32_bf16 v[72:75], v[158:161], v[222:225], v[72:75]
	global_load_lds_dwordx4 v0, s[68:69]
	v_mfma_f32_16x16x32_bf16 v[76:79], v[166:169], v[222:225], v[76:79]
	v_mfma_f32_16x16x32_bf16 v[80:83], v[214:217], v[222:225], v[80:83]
	v_mfma_f32_16x16x32_bf16 v[32:35], v[218:221], v[222:225], v[32:35]
	ds_read_b128 v[222:225], v6 offset:12288
	s_waitcnt lgkmcnt(3)
	v_mfma_f32_16x16x32_bf16 v[88:91], v[158:161], v[226:229], v[88:91]
	s_mov_b32 m0, s53
	v_mfma_f32_16x16x32_bf16 v[92:95], v[166:169], v[226:229], v[92:95]
	global_load_lds_dwordx4 v2, s[64:65]
	v_mfma_f32_16x16x32_bf16 v[96:99], v[214:217], v[226:229], v[96:99]
	v_mfma_f32_16x16x32_bf16 v[36:39], v[218:221], v[226:229], v[36:39]
	ds_read_b128 v[226:229], v6 offset:14336
	s_waitcnt lgkmcnt(3)
	v_mfma_f32_16x16x32_bf16 v[104:107], v[158:161], v[162:165], v[104:107]
	s_waitcnt lgkmcnt(2)
	v_mfma_f32_16x16x32_bf16 v[116:119], v[158:161], v[178:181], v[116:119]
	s_waitcnt lgkmcnt(1)
	s_mov_b32 m0, s54
	v_mfma_f32_16x16x32_bf16 v[128:131], v[158:161], v[222:225], v[128:131]
	global_load_lds_dwordx4 v2, s[68:69]
	s_waitcnt lgkmcnt(0)
	v_mfma_f32_16x16x32_bf16 v[100:103], v[158:161], v[226:229], v[100:103]
	ds_read_b128 v[158:161], v7 offset:33792
	v_mfma_f32_16x16x32_bf16 v[108:111], v[166:169], v[162:165], v[108:111]
	v_mfma_f32_16x16x32_bf16 v[120:123], v[166:169], v[178:181], v[120:123]
	v_mfma_f32_16x16x32_bf16 v[132:135], v[166:169], v[222:225], v[132:135]
	s_mov_b32 m0, s55
	v_mfma_f32_16x16x32_bf16 v[140:143], v[166:169], v[226:229], v[140:143]
	global_load_lds_dwordx4 v4, s[64:65]
	ds_read_b128 v[166:169], v6 offset:1024
	v_mfma_f32_16x16x32_bf16 v[112:115], v[214:217], v[162:165], v[112:115]
	v_mfma_f32_16x16x32_bf16 v[52:55], v[218:221], v[162:165], v[52:55]
	ds_read_b128 v[162:165], v7 offset:35840
	v_mfma_f32_16x16x32_bf16 v[124:127], v[214:217], v[178:181], v[124:127]
	v_mfma_f32_16x16x32_bf16 v[68:71], v[218:221], v[178:181], v[68:71]
	ds_read_b128 v[178:181], v6 offset:3072
	s_mov_b32 m0, s58
	v_mfma_f32_16x16x32_bf16 v[136:139], v[214:217], v[222:225], v[136:139]
	global_load_lds_dwordx4 v4, s[68:69]
	v_mfma_f32_16x16x32_bf16 v[84:87], v[218:221], v[222:225], v[84:87]
	ds_read_b128 v[222:225], v6 offset:5120
	v_mfma_f32_16x16x32_bf16 v[150:153], v[214:217], v[226:229], v[150:153]
	ds_read_b128 v[214:217], v7 offset:37888
	v_mfma_f32_16x16x32_bf16 v[154:157], v[218:221], v[226:229], v[154:157]
	ds_read_b128 v[218:221], v7 offset:39936
	ds_read_b128 v[226:229], v6 offset:7168
	s_waitcnt lgkmcnt(6)
	v_mfma_f32_16x16x32_bf16 v[40:43], v[158:161], v[166:169], v[40:43]
	s_waitcnt lgkmcnt(5)
	s_mov_b32 m0, s62
	v_mfma_f32_16x16x32_bf16 v[44:47], v[162:165], v[166:169], v[44:47]
	global_load_lds_dwordx4 v146, s[64:65]
	s_waitcnt lgkmcnt(4)
	v_mfma_f32_16x16x32_bf16 v[56:59], v[158:161], v[178:181], v[56:59]
	v_mfma_f32_16x16x32_bf16 v[60:63], v[162:165], v[178:181], v[60:63]
	s_waitcnt lgkmcnt(3)
	v_mfma_f32_16x16x32_bf16 v[72:75], v[158:161], v[222:225], v[72:75]
	v_mfma_f32_16x16x32_bf16 v[76:79], v[162:165], v[222:225], v[76:79]
	s_waitcnt lgkmcnt(2)
	s_mov_b32 m0, s63
	v_mfma_f32_16x16x32_bf16 v[48:51], v[214:217], v[166:169], v[48:51]
	global_load_lds_dwordx4 v146, s[68:69]
	s_waitcnt lgkmcnt(1)
	v_mfma_f32_16x16x32_bf16 v[174:177], v[218:221], v[166:169], v[174:177]
	ds_read_b128 v[166:169], v6 offset:9216
	v_mfma_f32_16x16x32_bf16 v[64:67], v[214:217], v[178:181], v[64:67]
	v_mfma_f32_16x16x32_bf16 v[170:173], v[218:221], v[178:181], v[170:173]
	ds_read_b128 v[178:181], v6 offset:11264
	v_mfma_f32_16x16x32_bf16 v[80:83], v[214:217], v[222:225], v[80:83]
	v_mfma_f32_16x16x32_bf16 v[32:35], v[218:221], v[222:225], v[32:35]
	ds_read_b128 v[222:225], v6 offset:13312
	s_waitcnt lgkmcnt(3)
	v_mfma_f32_16x16x32_bf16 v[88:91], v[158:161], v[226:229], v[88:91]
	v_mfma_f32_16x16x32_bf16 v[92:95], v[162:165], v[226:229], v[92:95]
	v_mfma_f32_16x16x32_bf16 v[96:99], v[214:217], v[226:229], v[96:99]
	v_mfma_f32_16x16x32_bf16 v[36:39], v[218:221], v[226:229], v[36:39]
	ds_read_b128 v[226:229], v6 offset:15360
	s_waitcnt lgkmcnt(3)
	v_mfma_f32_16x16x32_bf16 v[104:107], v[158:161], v[166:169], v[104:107]
	v_mfma_f32_16x16x32_bf16 v[108:111], v[162:165], v[166:169], v[108:111]
	v_mfma_f32_16x16x32_bf16 v[112:115], v[214:217], v[166:169], v[112:115]
	v_mfma_f32_16x16x32_bf16 v[52:55], v[218:221], v[166:169], v[52:55]
	s_waitcnt lgkmcnt(2)
	v_mfma_f32_16x16x32_bf16 v[116:119], v[158:161], v[178:181], v[116:119]
	v_mfma_f32_16x16x32_bf16 v[120:123], v[162:165], v[178:181], v[120:123]
	v_mfma_f32_16x16x32_bf16 v[124:127], v[214:217], v[178:181], v[124:127]
	v_mfma_f32_16x16x32_bf16 v[68:71], v[218:221], v[178:181], v[68:71]
	s_waitcnt lgkmcnt(1)
	v_mfma_f32_16x16x32_bf16 v[128:131], v[158:161], v[222:225], v[128:131]
	v_mfma_f32_16x16x32_bf16 v[132:135], v[162:165], v[222:225], v[132:135]
	v_mfma_f32_16x16x32_bf16 v[136:139], v[214:217], v[222:225], v[136:139]
	v_mfma_f32_16x16x32_bf16 v[84:87], v[218:221], v[222:225], v[84:87]
	s_waitcnt lgkmcnt(0)
	v_mfma_f32_16x16x32_bf16 v[100:103], v[158:161], v[226:229], v[100:103]
	v_mfma_f32_16x16x32_bf16 v[140:143], v[162:165], v[226:229], v[140:143]
	v_mfma_f32_16x16x32_bf16 v[150:153], v[214:217], v[226:229], v[150:153]
	v_mfma_f32_16x16x32_bf16 v[154:157], v[218:221], v[226:229], v[154:157]
	s_add_u32 s64, s0, 0x2300
	s_addc_u32 s65, s1, 0
	s_add_u32 s68, s14, 0x2300
	s_waitcnt vmcnt(0)
	s_barrier
	s_addc_u32 s69, s15, 0
	ds_read_b128 v[158:161], v8
	ds_read_b128 v[162:165], v12
	ds_read_b128 v[166:169], v9
	ds_read_b128 v[178:181], v13
	ds_read_b128 v[214:217], v11
	ds_read_b128 v[218:221], v10
	ds_read_b128 v[222:225], v14
	ds_read_b128 v[226:229], v15
	s_waitcnt lgkmcnt(6)
	v_mfma_f32_16x16x32_bf16 v[40:43], v[158:161], v[162:165], v[40:43]
	s_waitcnt lgkmcnt(5)
	v_mfma_f32_16x16x32_bf16 v[44:47], v[166:169], v[162:165], v[44:47]
	s_waitcnt lgkmcnt(4)
	v_mfma_f32_16x16x32_bf16 v[56:59], v[158:161], v[178:181], v[56:59]
	s_mov_b32 m0, s42
	v_mfma_f32_16x16x32_bf16 v[60:63], v[166:169], v[178:181], v[60:63]
	global_load_lds_dwordx4 v0, s[64:65]
	s_waitcnt lgkmcnt(3)
	v_mfma_f32_16x16x32_bf16 v[48:51], v[214:217], v[162:165], v[48:51]
	v_mfma_f32_16x16x32_bf16 v[64:67], v[214:217], v[178:181], v[64:67]
	s_waitcnt lgkmcnt(2)
	v_mfma_f32_16x16x32_bf16 v[174:177], v[218:221], v[162:165], v[174:177]
	ds_read_b128 v[162:165], v16
	v_mfma_f32_16x16x32_bf16 v[170:173], v[218:221], v[178:181], v[170:173]
	ds_read_b128 v[178:181], v17
	s_waitcnt lgkmcnt(3)
	s_mov_b32 m0, s43
	v_mfma_f32_16x16x32_bf16 v[72:75], v[158:161], v[222:225], v[72:75]
	global_load_lds_dwordx4 v0, s[68:69]
	v_mfma_f32_16x16x32_bf16 v[76:79], v[166:169], v[222:225], v[76:79]
	v_mfma_f32_16x16x32_bf16 v[80:83], v[214:217], v[222:225], v[80:83]
	v_mfma_f32_16x16x32_bf16 v[32:35], v[218:221], v[222:225], v[32:35]
	ds_read_b128 v[222:225], v18
	s_waitcnt lgkmcnt(3)
	v_mfma_f32_16x16x32_bf16 v[88:91], v[158:161], v[226:229], v[88:91]
	s_mov_b32 m0, s44
	v_mfma_f32_16x16x32_bf16 v[92:95], v[166:169], v[226:229], v[92:95]
	global_load_lds_dwordx4 v2, s[64:65]
	v_mfma_f32_16x16x32_bf16 v[96:99], v[214:217], v[226:229], v[96:99]
	v_mfma_f32_16x16x32_bf16 v[36:39], v[218:221], v[226:229], v[36:39]
	ds_read_b128 v[226:229], v19
	s_waitcnt lgkmcnt(3)
	v_mfma_f32_16x16x32_bf16 v[104:107], v[158:161], v[162:165], v[104:107]
	s_waitcnt lgkmcnt(2)
	v_mfma_f32_16x16x32_bf16 v[116:119], v[158:161], v[178:181], v[116:119]
	s_waitcnt lgkmcnt(1)
	s_mov_b32 m0, s45
	v_mfma_f32_16x16x32_bf16 v[128:131], v[158:161], v[222:225], v[128:131]
	global_load_lds_dwordx4 v2, s[68:69]
	s_waitcnt lgkmcnt(0)
	v_mfma_f32_16x16x32_bf16 v[100:103], v[158:161], v[226:229], v[100:103]
	ds_read_b128 v[158:161], v20
	v_mfma_f32_16x16x32_bf16 v[108:111], v[166:169], v[162:165], v[108:111]
	v_mfma_f32_16x16x32_bf16 v[120:123], v[166:169], v[178:181], v[120:123]
	v_mfma_f32_16x16x32_bf16 v[132:135], v[166:169], v[222:225], v[132:135]
	s_mov_b32 m0, s46
	v_mfma_f32_16x16x32_bf16 v[140:143], v[166:169], v[226:229], v[140:143]
	global_load_lds_dwordx4 v4, s[64:65]
	ds_read_b128 v[166:169], v24
	v_mfma_f32_16x16x32_bf16 v[112:115], v[214:217], v[162:165], v[112:115]
	v_mfma_f32_16x16x32_bf16 v[52:55], v[218:221], v[162:165], v[52:55]
	ds_read_b128 v[162:165], v21
	v_mfma_f32_16x16x32_bf16 v[124:127], v[214:217], v[178:181], v[124:127]
	v_mfma_f32_16x16x32_bf16 v[68:71], v[218:221], v[178:181], v[68:71]
	ds_read_b128 v[178:181], v25
	s_mov_b32 m0, s47
	v_mfma_f32_16x16x32_bf16 v[136:139], v[214:217], v[222:225], v[136:139]
	global_load_lds_dwordx4 v4, s[68:69]
	v_mfma_f32_16x16x32_bf16 v[84:87], v[218:221], v[222:225], v[84:87]
	ds_read_b128 v[222:225], v26
	v_mfma_f32_16x16x32_bf16 v[150:153], v[214:217], v[226:229], v[150:153]
	ds_read_b128 v[214:217], v23
	v_mfma_f32_16x16x32_bf16 v[154:157], v[218:221], v[226:229], v[154:157]
	ds_read_b128 v[218:221], v22
	ds_read_b128 v[226:229], v27
	s_waitcnt lgkmcnt(6)
	v_mfma_f32_16x16x32_bf16 v[40:43], v[158:161], v[166:169], v[40:43]
	s_waitcnt lgkmcnt(5)
	s_mov_b32 m0, s49
	v_mfma_f32_16x16x32_bf16 v[44:47], v[162:165], v[166:169], v[44:47]
	global_load_lds_dwordx4 v146, s[64:65]
	s_waitcnt lgkmcnt(4)
	v_mfma_f32_16x16x32_bf16 v[56:59], v[158:161], v[178:181], v[56:59]
	v_mfma_f32_16x16x32_bf16 v[60:63], v[162:165], v[178:181], v[60:63]
	s_waitcnt lgkmcnt(3)
	v_mfma_f32_16x16x32_bf16 v[72:75], v[158:161], v[222:225], v[72:75]
	v_mfma_f32_16x16x32_bf16 v[76:79], v[162:165], v[222:225], v[76:79]
	s_waitcnt lgkmcnt(2)
	s_mov_b32 m0, s50
	v_mfma_f32_16x16x32_bf16 v[48:51], v[214:217], v[166:169], v[48:51]
	global_load_lds_dwordx4 v146, s[68:69]
	s_waitcnt lgkmcnt(1)
	v_mfma_f32_16x16x32_bf16 v[174:177], v[218:221], v[166:169], v[174:177]
	ds_read_b128 v[166:169], v28
	v_mfma_f32_16x16x32_bf16 v[64:67], v[214:217], v[178:181], v[64:67]
	v_mfma_f32_16x16x32_bf16 v[170:173], v[218:221], v[178:181], v[170:173]
	ds_read_b128 v[178:181], v29
	v_mfma_f32_16x16x32_bf16 v[80:83], v[214:217], v[222:225], v[80:83]
	v_mfma_f32_16x16x32_bf16 v[32:35], v[218:221], v[222:225], v[32:35]
	ds_read_b128 v[222:225], v30
	s_waitcnt lgkmcnt(3)
	v_mfma_f32_16x16x32_bf16 v[88:91], v[158:161], v[226:229], v[88:91]
	v_mfma_f32_16x16x32_bf16 v[92:95], v[162:165], v[226:229], v[92:95]
	v_mfma_f32_16x16x32_bf16 v[96:99], v[214:217], v[226:229], v[96:99]
	v_mfma_f32_16x16x32_bf16 v[36:39], v[218:221], v[226:229], v[36:39]
	ds_read_b128 v[226:229], v31
	s_waitcnt lgkmcnt(3)
	v_mfma_f32_16x16x32_bf16 v[104:107], v[158:161], v[166:169], v[104:107]
	v_mfma_f32_16x16x32_bf16 v[108:111], v[162:165], v[166:169], v[108:111]
	v_mfma_f32_16x16x32_bf16 v[112:115], v[214:217], v[166:169], v[112:115]
	v_mfma_f32_16x16x32_bf16 v[52:55], v[218:221], v[166:169], v[52:55]
	s_waitcnt lgkmcnt(2)
	v_mfma_f32_16x16x32_bf16 v[116:119], v[158:161], v[178:181], v[116:119]
	v_mfma_f32_16x16x32_bf16 v[120:123], v[162:165], v[178:181], v[120:123]
	v_mfma_f32_16x16x32_bf16 v[124:127], v[214:217], v[178:181], v[124:127]
	v_mfma_f32_16x16x32_bf16 v[68:71], v[218:221], v[178:181], v[68:71]
	s_waitcnt lgkmcnt(1)
	v_mfma_f32_16x16x32_bf16 v[128:131], v[158:161], v[222:225], v[128:131]
	v_mfma_f32_16x16x32_bf16 v[132:135], v[162:165], v[222:225], v[132:135]
	v_mfma_f32_16x16x32_bf16 v[136:139], v[214:217], v[222:225], v[136:139]
	v_mfma_f32_16x16x32_bf16 v[84:87], v[218:221], v[222:225], v[84:87]
	s_waitcnt lgkmcnt(0)
	v_mfma_f32_16x16x32_bf16 v[100:103], v[158:161], v[226:229], v[100:103]
	v_mfma_f32_16x16x32_bf16 v[140:143], v[162:165], v[226:229], v[140:143]
	v_mfma_f32_16x16x32_bf16 v[150:153], v[214:217], v[226:229], v[150:153]
	v_mfma_f32_16x16x32_bf16 v[154:157], v[218:221], v[226:229], v[154:157]
	s_add_u32 s64, s0, 0x2380
	s_addc_u32 s65, s1, 0
	s_add_u32 s68, s14, 0x2380
	s_waitcnt vmcnt(0)
	s_barrier
	s_addc_u32 s69, s15, 0
	ds_read_b128 v[158:161], v7 offset:32768
	ds_read_b128 v[162:165], v6
	ds_read_b128 v[166:169], v7 offset:34816
	ds_read_b128 v[178:181], v6 offset:2048
	ds_read_b128 v[214:217], v7 offset:36864
	ds_read_b128 v[218:221], v7 offset:38912
	ds_read_b128 v[222:225], v6 offset:4096
	ds_read_b128 v[226:229], v6 offset:6144
	s_waitcnt lgkmcnt(6)
	v_mfma_f32_16x16x32_bf16 v[40:43], v[158:161], v[162:165], v[40:43]
	s_waitcnt lgkmcnt(5)
	v_mfma_f32_16x16x32_bf16 v[44:47], v[166:169], v[162:165], v[44:47]
	s_waitcnt lgkmcnt(4)
	v_mfma_f32_16x16x32_bf16 v[56:59], v[158:161], v[178:181], v[56:59]
	s_mov_b32 m0, s52
	v_mfma_f32_16x16x32_bf16 v[60:63], v[166:169], v[178:181], v[60:63]
	global_load_lds_dwordx4 v0, s[64:65]
	s_waitcnt lgkmcnt(3)
	v_mfma_f32_16x16x32_bf16 v[48:51], v[214:217], v[162:165], v[48:51]
	v_mfma_f32_16x16x32_bf16 v[64:67], v[214:217], v[178:181], v[64:67]
	s_waitcnt lgkmcnt(2)
	v_mfma_f32_16x16x32_bf16 v[174:177], v[218:221], v[162:165], v[174:177]
	ds_read_b128 v[162:165], v6 offset:8192
	v_mfma_f32_16x16x32_bf16 v[170:173], v[218:221], v[178:181], v[170:173]
	ds_read_b128 v[178:181], v6 offset:10240
	s_waitcnt lgkmcnt(3)
	s_mov_b32 m0, s51
	v_mfma_f32_16x16x32_bf16 v[72:75], v[158:161], v[222:225], v[72:75]
	global_load_lds_dwordx4 v0, s[68:69]
	v_mfma_f32_16x16x32_bf16 v[76:79], v[166:169], v[222:225], v[76:79]
	v_mfma_f32_16x16x32_bf16 v[80:83], v[214:217], v[222:225], v[80:83]
	v_mfma_f32_16x16x32_bf16 v[32:35], v[218:221], v[222:225], v[32:35]
	ds_read_b128 v[222:225], v6 offset:12288
	s_waitcnt lgkmcnt(3)
	v_mfma_f32_16x16x32_bf16 v[88:91], v[158:161], v[226:229], v[88:91]
	s_mov_b32 m0, s53
	v_mfma_f32_16x16x32_bf16 v[92:95], v[166:169], v[226:229], v[92:95]
	global_load_lds_dwordx4 v2, s[64:65]
	v_mfma_f32_16x16x32_bf16 v[96:99], v[214:217], v[226:229], v[96:99]
	v_mfma_f32_16x16x32_bf16 v[36:39], v[218:221], v[226:229], v[36:39]
	ds_read_b128 v[226:229], v6 offset:14336
	s_waitcnt lgkmcnt(3)
	v_mfma_f32_16x16x32_bf16 v[104:107], v[158:161], v[162:165], v[104:107]
	s_waitcnt lgkmcnt(2)
	v_mfma_f32_16x16x32_bf16 v[116:119], v[158:161], v[178:181], v[116:119]
	s_waitcnt lgkmcnt(1)
	s_mov_b32 m0, s54
	v_mfma_f32_16x16x32_bf16 v[128:131], v[158:161], v[222:225], v[128:131]
	global_load_lds_dwordx4 v2, s[68:69]
	s_waitcnt lgkmcnt(0)
	v_mfma_f32_16x16x32_bf16 v[100:103], v[158:161], v[226:229], v[100:103]
	ds_read_b128 v[158:161], v7 offset:33792
	v_mfma_f32_16x16x32_bf16 v[108:111], v[166:169], v[162:165], v[108:111]
	v_mfma_f32_16x16x32_bf16 v[120:123], v[166:169], v[178:181], v[120:123]
	v_mfma_f32_16x16x32_bf16 v[132:135], v[166:169], v[222:225], v[132:135]
	s_mov_b32 m0, s55
	v_mfma_f32_16x16x32_bf16 v[140:143], v[166:169], v[226:229], v[140:143]
	global_load_lds_dwordx4 v4, s[64:65]
	ds_read_b128 v[166:169], v6 offset:1024
	v_mfma_f32_16x16x32_bf16 v[112:115], v[214:217], v[162:165], v[112:115]
	v_mfma_f32_16x16x32_bf16 v[52:55], v[218:221], v[162:165], v[52:55]
	ds_read_b128 v[162:165], v7 offset:35840
	v_mfma_f32_16x16x32_bf16 v[124:127], v[214:217], v[178:181], v[124:127]
	v_mfma_f32_16x16x32_bf16 v[68:71], v[218:221], v[178:181], v[68:71]
	ds_read_b128 v[178:181], v6 offset:3072
	s_mov_b32 m0, s58
	v_mfma_f32_16x16x32_bf16 v[136:139], v[214:217], v[222:225], v[136:139]
	global_load_lds_dwordx4 v4, s[68:69]
	v_mfma_f32_16x16x32_bf16 v[84:87], v[218:221], v[222:225], v[84:87]
	ds_read_b128 v[222:225], v6 offset:5120
	v_mfma_f32_16x16x32_bf16 v[150:153], v[214:217], v[226:229], v[150:153]
	ds_read_b128 v[214:217], v7 offset:37888
	v_mfma_f32_16x16x32_bf16 v[154:157], v[218:221], v[226:229], v[154:157]
	ds_read_b128 v[218:221], v7 offset:39936
	ds_read_b128 v[226:229], v6 offset:7168
	s_waitcnt lgkmcnt(6)
	v_mfma_f32_16x16x32_bf16 v[40:43], v[158:161], v[166:169], v[40:43]
	s_waitcnt lgkmcnt(5)
	s_mov_b32 m0, s62
	v_mfma_f32_16x16x32_bf16 v[44:47], v[162:165], v[166:169], v[44:47]
	global_load_lds_dwordx4 v146, s[64:65]
	s_waitcnt lgkmcnt(4)
	v_mfma_f32_16x16x32_bf16 v[56:59], v[158:161], v[178:181], v[56:59]
	v_mfma_f32_16x16x32_bf16 v[60:63], v[162:165], v[178:181], v[60:63]
	s_waitcnt lgkmcnt(3)
	v_mfma_f32_16x16x32_bf16 v[72:75], v[158:161], v[222:225], v[72:75]
	v_mfma_f32_16x16x32_bf16 v[76:79], v[162:165], v[222:225], v[76:79]
	s_waitcnt lgkmcnt(2)
	s_mov_b32 m0, s63
	v_mfma_f32_16x16x32_bf16 v[48:51], v[214:217], v[166:169], v[48:51]
	global_load_lds_dwordx4 v146, s[68:69]
	s_waitcnt lgkmcnt(1)
	v_mfma_f32_16x16x32_bf16 v[174:177], v[218:221], v[166:169], v[174:177]
	ds_read_b128 v[166:169], v6 offset:9216
	v_mfma_f32_16x16x32_bf16 v[64:67], v[214:217], v[178:181], v[64:67]
	v_mfma_f32_16x16x32_bf16 v[170:173], v[218:221], v[178:181], v[170:173]
	ds_read_b128 v[178:181], v6 offset:11264
	v_mfma_f32_16x16x32_bf16 v[80:83], v[214:217], v[222:225], v[80:83]
	v_mfma_f32_16x16x32_bf16 v[32:35], v[218:221], v[222:225], v[32:35]
	ds_read_b128 v[222:225], v6 offset:13312
	s_waitcnt lgkmcnt(3)
	v_mfma_f32_16x16x32_bf16 v[88:91], v[158:161], v[226:229], v[88:91]
	v_mfma_f32_16x16x32_bf16 v[92:95], v[162:165], v[226:229], v[92:95]
	v_mfma_f32_16x16x32_bf16 v[96:99], v[214:217], v[226:229], v[96:99]
	v_mfma_f32_16x16x32_bf16 v[36:39], v[218:221], v[226:229], v[36:39]
	ds_read_b128 v[226:229], v6 offset:15360
	s_waitcnt lgkmcnt(3)
	v_mfma_f32_16x16x32_bf16 v[104:107], v[158:161], v[166:169], v[104:107]
	v_mfma_f32_16x16x32_bf16 v[108:111], v[162:165], v[166:169], v[108:111]
	v_mfma_f32_16x16x32_bf16 v[112:115], v[214:217], v[166:169], v[112:115]
	v_mfma_f32_16x16x32_bf16 v[52:55], v[218:221], v[166:169], v[52:55]
	s_waitcnt lgkmcnt(2)
	v_mfma_f32_16x16x32_bf16 v[116:119], v[158:161], v[178:181], v[116:119]
	v_mfma_f32_16x16x32_bf16 v[120:123], v[162:165], v[178:181], v[120:123]
	v_mfma_f32_16x16x32_bf16 v[124:127], v[214:217], v[178:181], v[124:127]
	v_mfma_f32_16x16x32_bf16 v[68:71], v[218:221], v[178:181], v[68:71]
	s_waitcnt lgkmcnt(1)
	v_mfma_f32_16x16x32_bf16 v[128:131], v[158:161], v[222:225], v[128:131]
	v_mfma_f32_16x16x32_bf16 v[132:135], v[162:165], v[222:225], v[132:135]
	v_mfma_f32_16x16x32_bf16 v[136:139], v[214:217], v[222:225], v[136:139]
	v_mfma_f32_16x16x32_bf16 v[84:87], v[218:221], v[222:225], v[84:87]
	s_waitcnt lgkmcnt(0)
	v_mfma_f32_16x16x32_bf16 v[100:103], v[158:161], v[226:229], v[100:103]
	v_mfma_f32_16x16x32_bf16 v[140:143], v[162:165], v[226:229], v[140:143]
	v_mfma_f32_16x16x32_bf16 v[150:153], v[214:217], v[226:229], v[150:153]
	v_mfma_f32_16x16x32_bf16 v[154:157], v[218:221], v[226:229], v[154:157]
	s_add_u32 s64, s0, 0x2400
	s_addc_u32 s65, s1, 0
	s_add_u32 s68, s14, 0x2400
	s_waitcnt vmcnt(0)
	s_barrier
	s_addc_u32 s69, s15, 0
	ds_read_b128 v[158:161], v8
	ds_read_b128 v[162:165], v12
	ds_read_b128 v[166:169], v9
	ds_read_b128 v[178:181], v13
	ds_read_b128 v[214:217], v11
	ds_read_b128 v[218:221], v10
	ds_read_b128 v[222:225], v14
	ds_read_b128 v[226:229], v15
	s_waitcnt lgkmcnt(6)
	v_mfma_f32_16x16x32_bf16 v[40:43], v[158:161], v[162:165], v[40:43]
	s_waitcnt lgkmcnt(5)
	v_mfma_f32_16x16x32_bf16 v[44:47], v[166:169], v[162:165], v[44:47]
	s_waitcnt lgkmcnt(4)
	v_mfma_f32_16x16x32_bf16 v[56:59], v[158:161], v[178:181], v[56:59]
	s_mov_b32 m0, s42
	v_mfma_f32_16x16x32_bf16 v[60:63], v[166:169], v[178:181], v[60:63]
	global_load_lds_dwordx4 v0, s[64:65]
	s_waitcnt lgkmcnt(3)
	v_mfma_f32_16x16x32_bf16 v[48:51], v[214:217], v[162:165], v[48:51]
	v_mfma_f32_16x16x32_bf16 v[64:67], v[214:217], v[178:181], v[64:67]
	s_waitcnt lgkmcnt(2)
	v_mfma_f32_16x16x32_bf16 v[174:177], v[218:221], v[162:165], v[174:177]
	ds_read_b128 v[162:165], v16
	v_mfma_f32_16x16x32_bf16 v[170:173], v[218:221], v[178:181], v[170:173]
	ds_read_b128 v[178:181], v17
	s_waitcnt lgkmcnt(3)
	s_mov_b32 m0, s43
	v_mfma_f32_16x16x32_bf16 v[72:75], v[158:161], v[222:225], v[72:75]
	global_load_lds_dwordx4 v0, s[68:69]
	v_mfma_f32_16x16x32_bf16 v[76:79], v[166:169], v[222:225], v[76:79]
	v_mfma_f32_16x16x32_bf16 v[80:83], v[214:217], v[222:225], v[80:83]
	v_mfma_f32_16x16x32_bf16 v[32:35], v[218:221], v[222:225], v[32:35]
	ds_read_b128 v[222:225], v18
	s_waitcnt lgkmcnt(3)
	v_mfma_f32_16x16x32_bf16 v[88:91], v[158:161], v[226:229], v[88:91]
	s_mov_b32 m0, s44
	v_mfma_f32_16x16x32_bf16 v[92:95], v[166:169], v[226:229], v[92:95]
	global_load_lds_dwordx4 v2, s[64:65]
	v_mfma_f32_16x16x32_bf16 v[96:99], v[214:217], v[226:229], v[96:99]
	v_mfma_f32_16x16x32_bf16 v[36:39], v[218:221], v[226:229], v[36:39]
	ds_read_b128 v[226:229], v19
	s_waitcnt lgkmcnt(3)
	v_mfma_f32_16x16x32_bf16 v[104:107], v[158:161], v[162:165], v[104:107]
	s_waitcnt lgkmcnt(2)
	v_mfma_f32_16x16x32_bf16 v[116:119], v[158:161], v[178:181], v[116:119]
	s_waitcnt lgkmcnt(1)
	s_mov_b32 m0, s45
	v_mfma_f32_16x16x32_bf16 v[128:131], v[158:161], v[222:225], v[128:131]
	global_load_lds_dwordx4 v2, s[68:69]
	s_waitcnt lgkmcnt(0)
	v_mfma_f32_16x16x32_bf16 v[100:103], v[158:161], v[226:229], v[100:103]
	ds_read_b128 v[158:161], v20
	v_mfma_f32_16x16x32_bf16 v[108:111], v[166:169], v[162:165], v[108:111]
	v_mfma_f32_16x16x32_bf16 v[120:123], v[166:169], v[178:181], v[120:123]
	v_mfma_f32_16x16x32_bf16 v[132:135], v[166:169], v[222:225], v[132:135]
	s_mov_b32 m0, s46
	v_mfma_f32_16x16x32_bf16 v[140:143], v[166:169], v[226:229], v[140:143]
	global_load_lds_dwordx4 v4, s[64:65]
	ds_read_b128 v[166:169], v24
	v_mfma_f32_16x16x32_bf16 v[112:115], v[214:217], v[162:165], v[112:115]
	v_mfma_f32_16x16x32_bf16 v[52:55], v[218:221], v[162:165], v[52:55]
	ds_read_b128 v[162:165], v21
	v_mfma_f32_16x16x32_bf16 v[124:127], v[214:217], v[178:181], v[124:127]
	v_mfma_f32_16x16x32_bf16 v[68:71], v[218:221], v[178:181], v[68:71]
	ds_read_b128 v[178:181], v25
	s_mov_b32 m0, s47
	v_mfma_f32_16x16x32_bf16 v[136:139], v[214:217], v[222:225], v[136:139]
	global_load_lds_dwordx4 v4, s[68:69]
	v_mfma_f32_16x16x32_bf16 v[84:87], v[218:221], v[222:225], v[84:87]
	ds_read_b128 v[222:225], v26
	v_mfma_f32_16x16x32_bf16 v[150:153], v[214:217], v[226:229], v[150:153]
	ds_read_b128 v[214:217], v23
	v_mfma_f32_16x16x32_bf16 v[154:157], v[218:221], v[226:229], v[154:157]
	ds_read_b128 v[218:221], v22
	ds_read_b128 v[226:229], v27
	s_waitcnt lgkmcnt(6)
	v_mfma_f32_16x16x32_bf16 v[40:43], v[158:161], v[166:169], v[40:43]
	s_waitcnt lgkmcnt(5)
	s_mov_b32 m0, s49
	v_mfma_f32_16x16x32_bf16 v[44:47], v[162:165], v[166:169], v[44:47]
	global_load_lds_dwordx4 v146, s[64:65]
	s_waitcnt lgkmcnt(4)
	v_mfma_f32_16x16x32_bf16 v[56:59], v[158:161], v[178:181], v[56:59]
	v_mfma_f32_16x16x32_bf16 v[60:63], v[162:165], v[178:181], v[60:63]
	s_waitcnt lgkmcnt(3)
	v_mfma_f32_16x16x32_bf16 v[72:75], v[158:161], v[222:225], v[72:75]
	v_mfma_f32_16x16x32_bf16 v[76:79], v[162:165], v[222:225], v[76:79]
	s_waitcnt lgkmcnt(2)
	s_mov_b32 m0, s50
	v_mfma_f32_16x16x32_bf16 v[48:51], v[214:217], v[166:169], v[48:51]
	global_load_lds_dwordx4 v146, s[68:69]
	s_waitcnt lgkmcnt(1)
	v_mfma_f32_16x16x32_bf16 v[174:177], v[218:221], v[166:169], v[174:177]
	ds_read_b128 v[166:169], v28
	v_mfma_f32_16x16x32_bf16 v[64:67], v[214:217], v[178:181], v[64:67]
	v_mfma_f32_16x16x32_bf16 v[170:173], v[218:221], v[178:181], v[170:173]
	ds_read_b128 v[178:181], v29
	v_mfma_f32_16x16x32_bf16 v[80:83], v[214:217], v[222:225], v[80:83]
	v_mfma_f32_16x16x32_bf16 v[32:35], v[218:221], v[222:225], v[32:35]
	ds_read_b128 v[222:225], v30
	s_waitcnt lgkmcnt(3)
	v_mfma_f32_16x16x32_bf16 v[88:91], v[158:161], v[226:229], v[88:91]
	v_mfma_f32_16x16x32_bf16 v[92:95], v[162:165], v[226:229], v[92:95]
	v_mfma_f32_16x16x32_bf16 v[96:99], v[214:217], v[226:229], v[96:99]
	v_mfma_f32_16x16x32_bf16 v[36:39], v[218:221], v[226:229], v[36:39]
	ds_read_b128 v[226:229], v31
	s_waitcnt lgkmcnt(3)
	v_mfma_f32_16x16x32_bf16 v[104:107], v[158:161], v[166:169], v[104:107]
	v_mfma_f32_16x16x32_bf16 v[108:111], v[162:165], v[166:169], v[108:111]
	v_mfma_f32_16x16x32_bf16 v[112:115], v[214:217], v[166:169], v[112:115]
	v_mfma_f32_16x16x32_bf16 v[52:55], v[218:221], v[166:169], v[52:55]
	s_waitcnt lgkmcnt(2)
	v_mfma_f32_16x16x32_bf16 v[116:119], v[158:161], v[178:181], v[116:119]
	v_mfma_f32_16x16x32_bf16 v[120:123], v[162:165], v[178:181], v[120:123]
	v_mfma_f32_16x16x32_bf16 v[124:127], v[214:217], v[178:181], v[124:127]
	v_mfma_f32_16x16x32_bf16 v[68:71], v[218:221], v[178:181], v[68:71]
	s_waitcnt lgkmcnt(1)
	v_mfma_f32_16x16x32_bf16 v[128:131], v[158:161], v[222:225], v[128:131]
	v_mfma_f32_16x16x32_bf16 v[132:135], v[162:165], v[222:225], v[132:135]
	v_mfma_f32_16x16x32_bf16 v[136:139], v[214:217], v[222:225], v[136:139]
	v_mfma_f32_16x16x32_bf16 v[84:87], v[218:221], v[222:225], v[84:87]
	s_waitcnt lgkmcnt(0)
	v_mfma_f32_16x16x32_bf16 v[100:103], v[158:161], v[226:229], v[100:103]
	v_mfma_f32_16x16x32_bf16 v[140:143], v[162:165], v[226:229], v[140:143]
	v_mfma_f32_16x16x32_bf16 v[150:153], v[214:217], v[226:229], v[150:153]
	v_mfma_f32_16x16x32_bf16 v[154:157], v[218:221], v[226:229], v[154:157]
	s_add_u32 s64, s0, 0x2480
	s_addc_u32 s65, s1, 0
	s_add_u32 s68, s14, 0x2480
	s_waitcnt vmcnt(0)
	s_barrier
	s_addc_u32 s69, s15, 0
	ds_read_b128 v[158:161], v7 offset:32768
	ds_read_b128 v[162:165], v6
	ds_read_b128 v[166:169], v7 offset:34816
	ds_read_b128 v[178:181], v6 offset:2048
	ds_read_b128 v[214:217], v7 offset:36864
	ds_read_b128 v[218:221], v7 offset:38912
	ds_read_b128 v[222:225], v6 offset:4096
	ds_read_b128 v[226:229], v6 offset:6144
	s_waitcnt lgkmcnt(6)
	v_mfma_f32_16x16x32_bf16 v[40:43], v[158:161], v[162:165], v[40:43]
	s_waitcnt lgkmcnt(5)
	v_mfma_f32_16x16x32_bf16 v[44:47], v[166:169], v[162:165], v[44:47]
	s_waitcnt lgkmcnt(4)
	v_mfma_f32_16x16x32_bf16 v[56:59], v[158:161], v[178:181], v[56:59]
	s_mov_b32 m0, s52
	v_mfma_f32_16x16x32_bf16 v[60:63], v[166:169], v[178:181], v[60:63]
	global_load_lds_dwordx4 v0, s[64:65]
	s_waitcnt lgkmcnt(3)
	v_mfma_f32_16x16x32_bf16 v[48:51], v[214:217], v[162:165], v[48:51]
	v_mfma_f32_16x16x32_bf16 v[64:67], v[214:217], v[178:181], v[64:67]
	s_waitcnt lgkmcnt(2)
	v_mfma_f32_16x16x32_bf16 v[174:177], v[218:221], v[162:165], v[174:177]
	ds_read_b128 v[162:165], v6 offset:8192
	v_mfma_f32_16x16x32_bf16 v[170:173], v[218:221], v[178:181], v[170:173]
	ds_read_b128 v[178:181], v6 offset:10240
	s_waitcnt lgkmcnt(3)
	s_mov_b32 m0, s51
	v_mfma_f32_16x16x32_bf16 v[72:75], v[158:161], v[222:225], v[72:75]
	global_load_lds_dwordx4 v0, s[68:69]
	v_mfma_f32_16x16x32_bf16 v[76:79], v[166:169], v[222:225], v[76:79]
	v_mfma_f32_16x16x32_bf16 v[80:83], v[214:217], v[222:225], v[80:83]
	v_mfma_f32_16x16x32_bf16 v[32:35], v[218:221], v[222:225], v[32:35]
	ds_read_b128 v[222:225], v6 offset:12288
	s_waitcnt lgkmcnt(3)
	v_mfma_f32_16x16x32_bf16 v[88:91], v[158:161], v[226:229], v[88:91]
	s_mov_b32 m0, s53
	v_mfma_f32_16x16x32_bf16 v[92:95], v[166:169], v[226:229], v[92:95]
	global_load_lds_dwordx4 v2, s[64:65]
	v_mfma_f32_16x16x32_bf16 v[96:99], v[214:217], v[226:229], v[96:99]
	v_mfma_f32_16x16x32_bf16 v[36:39], v[218:221], v[226:229], v[36:39]
	ds_read_b128 v[226:229], v6 offset:14336
	s_waitcnt lgkmcnt(3)
	v_mfma_f32_16x16x32_bf16 v[104:107], v[158:161], v[162:165], v[104:107]
	s_waitcnt lgkmcnt(2)
	v_mfma_f32_16x16x32_bf16 v[116:119], v[158:161], v[178:181], v[116:119]
	s_waitcnt lgkmcnt(1)
	s_mov_b32 m0, s54
	v_mfma_f32_16x16x32_bf16 v[128:131], v[158:161], v[222:225], v[128:131]
	global_load_lds_dwordx4 v2, s[68:69]
	s_waitcnt lgkmcnt(0)
	v_mfma_f32_16x16x32_bf16 v[100:103], v[158:161], v[226:229], v[100:103]
	ds_read_b128 v[158:161], v7 offset:33792
	v_mfma_f32_16x16x32_bf16 v[108:111], v[166:169], v[162:165], v[108:111]
	v_mfma_f32_16x16x32_bf16 v[120:123], v[166:169], v[178:181], v[120:123]
	v_mfma_f32_16x16x32_bf16 v[132:135], v[166:169], v[222:225], v[132:135]
	s_mov_b32 m0, s55
	v_mfma_f32_16x16x32_bf16 v[140:143], v[166:169], v[226:229], v[140:143]
	global_load_lds_dwordx4 v4, s[64:65]
	ds_read_b128 v[166:169], v6 offset:1024
	v_mfma_f32_16x16x32_bf16 v[112:115], v[214:217], v[162:165], v[112:115]
	v_mfma_f32_16x16x32_bf16 v[52:55], v[218:221], v[162:165], v[52:55]
	ds_read_b128 v[162:165], v7 offset:35840
	v_mfma_f32_16x16x32_bf16 v[124:127], v[214:217], v[178:181], v[124:127]
	v_mfma_f32_16x16x32_bf16 v[68:71], v[218:221], v[178:181], v[68:71]
	ds_read_b128 v[178:181], v6 offset:3072
	s_mov_b32 m0, s58
	v_mfma_f32_16x16x32_bf16 v[136:139], v[214:217], v[222:225], v[136:139]
	global_load_lds_dwordx4 v4, s[68:69]
	v_mfma_f32_16x16x32_bf16 v[84:87], v[218:221], v[222:225], v[84:87]
	ds_read_b128 v[222:225], v6 offset:5120
	v_mfma_f32_16x16x32_bf16 v[150:153], v[214:217], v[226:229], v[150:153]
	ds_read_b128 v[214:217], v7 offset:37888
	v_mfma_f32_16x16x32_bf16 v[154:157], v[218:221], v[226:229], v[154:157]
	ds_read_b128 v[218:221], v7 offset:39936
	ds_read_b128 v[226:229], v6 offset:7168
	s_waitcnt lgkmcnt(6)
	v_mfma_f32_16x16x32_bf16 v[40:43], v[158:161], v[166:169], v[40:43]
	s_waitcnt lgkmcnt(5)
	s_mov_b32 m0, s62
	v_mfma_f32_16x16x32_bf16 v[44:47], v[162:165], v[166:169], v[44:47]
	global_load_lds_dwordx4 v146, s[64:65]
	s_waitcnt lgkmcnt(4)
	v_mfma_f32_16x16x32_bf16 v[56:59], v[158:161], v[178:181], v[56:59]
	v_mfma_f32_16x16x32_bf16 v[60:63], v[162:165], v[178:181], v[60:63]
	s_waitcnt lgkmcnt(3)
	v_mfma_f32_16x16x32_bf16 v[72:75], v[158:161], v[222:225], v[72:75]
	v_mfma_f32_16x16x32_bf16 v[76:79], v[162:165], v[222:225], v[76:79]
	s_waitcnt lgkmcnt(2)
	s_mov_b32 m0, s63
	v_mfma_f32_16x16x32_bf16 v[48:51], v[214:217], v[166:169], v[48:51]
	global_load_lds_dwordx4 v146, s[68:69]
	s_waitcnt lgkmcnt(1)
	v_mfma_f32_16x16x32_bf16 v[174:177], v[218:221], v[166:169], v[174:177]
	ds_read_b128 v[166:169], v6 offset:9216
	v_mfma_f32_16x16x32_bf16 v[64:67], v[214:217], v[178:181], v[64:67]
	v_mfma_f32_16x16x32_bf16 v[170:173], v[218:221], v[178:181], v[170:173]
	ds_read_b128 v[178:181], v6 offset:11264
	v_mfma_f32_16x16x32_bf16 v[80:83], v[214:217], v[222:225], v[80:83]
	v_mfma_f32_16x16x32_bf16 v[32:35], v[218:221], v[222:225], v[32:35]
	ds_read_b128 v[222:225], v6 offset:13312
	s_waitcnt lgkmcnt(3)
	v_mfma_f32_16x16x32_bf16 v[88:91], v[158:161], v[226:229], v[88:91]
	v_mfma_f32_16x16x32_bf16 v[92:95], v[162:165], v[226:229], v[92:95]
	v_mfma_f32_16x16x32_bf16 v[96:99], v[214:217], v[226:229], v[96:99]
	v_mfma_f32_16x16x32_bf16 v[36:39], v[218:221], v[226:229], v[36:39]
	ds_read_b128 v[226:229], v6 offset:15360
	s_waitcnt lgkmcnt(3)
	v_mfma_f32_16x16x32_bf16 v[104:107], v[158:161], v[166:169], v[104:107]
	v_mfma_f32_16x16x32_bf16 v[108:111], v[162:165], v[166:169], v[108:111]
	v_mfma_f32_16x16x32_bf16 v[112:115], v[214:217], v[166:169], v[112:115]
	v_mfma_f32_16x16x32_bf16 v[52:55], v[218:221], v[166:169], v[52:55]
	s_waitcnt lgkmcnt(2)
	v_mfma_f32_16x16x32_bf16 v[116:119], v[158:161], v[178:181], v[116:119]
	v_mfma_f32_16x16x32_bf16 v[120:123], v[162:165], v[178:181], v[120:123]
	v_mfma_f32_16x16x32_bf16 v[124:127], v[214:217], v[178:181], v[124:127]
	v_mfma_f32_16x16x32_bf16 v[68:71], v[218:221], v[178:181], v[68:71]
	s_waitcnt lgkmcnt(1)
	v_mfma_f32_16x16x32_bf16 v[128:131], v[158:161], v[222:225], v[128:131]
	v_mfma_f32_16x16x32_bf16 v[132:135], v[162:165], v[222:225], v[132:135]
	v_mfma_f32_16x16x32_bf16 v[136:139], v[214:217], v[222:225], v[136:139]
	v_mfma_f32_16x16x32_bf16 v[84:87], v[218:221], v[222:225], v[84:87]
	s_waitcnt lgkmcnt(0)
	v_mfma_f32_16x16x32_bf16 v[100:103], v[158:161], v[226:229], v[100:103]
	v_mfma_f32_16x16x32_bf16 v[140:143], v[162:165], v[226:229], v[140:143]
	v_mfma_f32_16x16x32_bf16 v[150:153], v[214:217], v[226:229], v[150:153]
	v_mfma_f32_16x16x32_bf16 v[154:157], v[218:221], v[226:229], v[154:157]
	s_add_u32 s64, s0, 0x2500
	s_addc_u32 s65, s1, 0
	s_add_u32 s68, s14, 0x2500
	s_waitcnt vmcnt(0)
	s_barrier
	s_addc_u32 s69, s15, 0
	ds_read_b128 v[158:161], v8
	ds_read_b128 v[162:165], v12
	ds_read_b128 v[166:169], v9
	ds_read_b128 v[178:181], v13
	ds_read_b128 v[214:217], v11
	ds_read_b128 v[218:221], v10
	ds_read_b128 v[222:225], v14
	ds_read_b128 v[226:229], v15
	s_waitcnt lgkmcnt(6)
	v_mfma_f32_16x16x32_bf16 v[40:43], v[158:161], v[162:165], v[40:43]
	s_waitcnt lgkmcnt(5)
	v_mfma_f32_16x16x32_bf16 v[44:47], v[166:169], v[162:165], v[44:47]
	s_waitcnt lgkmcnt(4)
	v_mfma_f32_16x16x32_bf16 v[56:59], v[158:161], v[178:181], v[56:59]
	s_mov_b32 m0, s42
	v_mfma_f32_16x16x32_bf16 v[60:63], v[166:169], v[178:181], v[60:63]
	global_load_lds_dwordx4 v0, s[64:65]
	s_waitcnt lgkmcnt(3)
	v_mfma_f32_16x16x32_bf16 v[48:51], v[214:217], v[162:165], v[48:51]
	v_mfma_f32_16x16x32_bf16 v[64:67], v[214:217], v[178:181], v[64:67]
	s_waitcnt lgkmcnt(2)
	v_mfma_f32_16x16x32_bf16 v[174:177], v[218:221], v[162:165], v[174:177]
	ds_read_b128 v[162:165], v16
	v_mfma_f32_16x16x32_bf16 v[170:173], v[218:221], v[178:181], v[170:173]
	ds_read_b128 v[178:181], v17
	s_waitcnt lgkmcnt(3)
	s_mov_b32 m0, s43
	v_mfma_f32_16x16x32_bf16 v[72:75], v[158:161], v[222:225], v[72:75]
	global_load_lds_dwordx4 v0, s[68:69]
	v_mfma_f32_16x16x32_bf16 v[76:79], v[166:169], v[222:225], v[76:79]
	v_mfma_f32_16x16x32_bf16 v[80:83], v[214:217], v[222:225], v[80:83]
	v_mfma_f32_16x16x32_bf16 v[32:35], v[218:221], v[222:225], v[32:35]
	ds_read_b128 v[222:225], v18
	s_waitcnt lgkmcnt(3)
	v_mfma_f32_16x16x32_bf16 v[88:91], v[158:161], v[226:229], v[88:91]
	s_mov_b32 m0, s44
	v_mfma_f32_16x16x32_bf16 v[92:95], v[166:169], v[226:229], v[92:95]
	global_load_lds_dwordx4 v2, s[64:65]
	v_mfma_f32_16x16x32_bf16 v[96:99], v[214:217], v[226:229], v[96:99]
	v_mfma_f32_16x16x32_bf16 v[36:39], v[218:221], v[226:229], v[36:39]
	ds_read_b128 v[226:229], v19
	s_waitcnt lgkmcnt(3)
	v_mfma_f32_16x16x32_bf16 v[104:107], v[158:161], v[162:165], v[104:107]
	s_waitcnt lgkmcnt(2)
	v_mfma_f32_16x16x32_bf16 v[116:119], v[158:161], v[178:181], v[116:119]
	s_waitcnt lgkmcnt(1)
	s_mov_b32 m0, s45
	v_mfma_f32_16x16x32_bf16 v[128:131], v[158:161], v[222:225], v[128:131]
	global_load_lds_dwordx4 v2, s[68:69]
	s_waitcnt lgkmcnt(0)
	v_mfma_f32_16x16x32_bf16 v[100:103], v[158:161], v[226:229], v[100:103]
	ds_read_b128 v[158:161], v20
	v_mfma_f32_16x16x32_bf16 v[108:111], v[166:169], v[162:165], v[108:111]
	v_mfma_f32_16x16x32_bf16 v[120:123], v[166:169], v[178:181], v[120:123]
	v_mfma_f32_16x16x32_bf16 v[132:135], v[166:169], v[222:225], v[132:135]
	s_mov_b32 m0, s46
	v_mfma_f32_16x16x32_bf16 v[140:143], v[166:169], v[226:229], v[140:143]
	global_load_lds_dwordx4 v4, s[64:65]
	ds_read_b128 v[166:169], v24
	v_mfma_f32_16x16x32_bf16 v[112:115], v[214:217], v[162:165], v[112:115]
	v_mfma_f32_16x16x32_bf16 v[52:55], v[218:221], v[162:165], v[52:55]
	ds_read_b128 v[162:165], v21
	v_mfma_f32_16x16x32_bf16 v[124:127], v[214:217], v[178:181], v[124:127]
	v_mfma_f32_16x16x32_bf16 v[68:71], v[218:221], v[178:181], v[68:71]
	ds_read_b128 v[178:181], v25
	s_mov_b32 m0, s47
	v_mfma_f32_16x16x32_bf16 v[136:139], v[214:217], v[222:225], v[136:139]
	global_load_lds_dwordx4 v4, s[68:69]
	v_mfma_f32_16x16x32_bf16 v[84:87], v[218:221], v[222:225], v[84:87]
	ds_read_b128 v[222:225], v26
	v_mfma_f32_16x16x32_bf16 v[150:153], v[214:217], v[226:229], v[150:153]
	ds_read_b128 v[214:217], v23
	v_mfma_f32_16x16x32_bf16 v[154:157], v[218:221], v[226:229], v[154:157]
	ds_read_b128 v[218:221], v22
	ds_read_b128 v[226:229], v27
	s_waitcnt lgkmcnt(6)
	v_mfma_f32_16x16x32_bf16 v[40:43], v[158:161], v[166:169], v[40:43]
	s_waitcnt lgkmcnt(5)
	s_mov_b32 m0, s49
	v_mfma_f32_16x16x32_bf16 v[44:47], v[162:165], v[166:169], v[44:47]
	global_load_lds_dwordx4 v146, s[64:65]
	s_waitcnt lgkmcnt(4)
	v_mfma_f32_16x16x32_bf16 v[56:59], v[158:161], v[178:181], v[56:59]
	v_mfma_f32_16x16x32_bf16 v[60:63], v[162:165], v[178:181], v[60:63]
	s_waitcnt lgkmcnt(3)
	v_mfma_f32_16x16x32_bf16 v[72:75], v[158:161], v[222:225], v[72:75]
	v_mfma_f32_16x16x32_bf16 v[76:79], v[162:165], v[222:225], v[76:79]
	s_waitcnt lgkmcnt(2)
	s_mov_b32 m0, s50
	v_mfma_f32_16x16x32_bf16 v[48:51], v[214:217], v[166:169], v[48:51]
	global_load_lds_dwordx4 v146, s[68:69]
	s_waitcnt lgkmcnt(1)
	v_mfma_f32_16x16x32_bf16 v[174:177], v[218:221], v[166:169], v[174:177]
	ds_read_b128 v[166:169], v28
	v_mfma_f32_16x16x32_bf16 v[64:67], v[214:217], v[178:181], v[64:67]
	v_mfma_f32_16x16x32_bf16 v[170:173], v[218:221], v[178:181], v[170:173]
	ds_read_b128 v[178:181], v29
	v_mfma_f32_16x16x32_bf16 v[80:83], v[214:217], v[222:225], v[80:83]
	v_mfma_f32_16x16x32_bf16 v[32:35], v[218:221], v[222:225], v[32:35]
	ds_read_b128 v[222:225], v30
	s_waitcnt lgkmcnt(3)
	v_mfma_f32_16x16x32_bf16 v[88:91], v[158:161], v[226:229], v[88:91]
	v_mfma_f32_16x16x32_bf16 v[92:95], v[162:165], v[226:229], v[92:95]
	v_mfma_f32_16x16x32_bf16 v[96:99], v[214:217], v[226:229], v[96:99]
	v_mfma_f32_16x16x32_bf16 v[36:39], v[218:221], v[226:229], v[36:39]
	ds_read_b128 v[226:229], v31
	s_waitcnt lgkmcnt(3)
	v_mfma_f32_16x16x32_bf16 v[104:107], v[158:161], v[166:169], v[104:107]
	v_mfma_f32_16x16x32_bf16 v[108:111], v[162:165], v[166:169], v[108:111]
	v_mfma_f32_16x16x32_bf16 v[112:115], v[214:217], v[166:169], v[112:115]
	v_mfma_f32_16x16x32_bf16 v[52:55], v[218:221], v[166:169], v[52:55]
	s_waitcnt lgkmcnt(2)
	v_mfma_f32_16x16x32_bf16 v[116:119], v[158:161], v[178:181], v[116:119]
	v_mfma_f32_16x16x32_bf16 v[120:123], v[162:165], v[178:181], v[120:123]
	v_mfma_f32_16x16x32_bf16 v[124:127], v[214:217], v[178:181], v[124:127]
	v_mfma_f32_16x16x32_bf16 v[68:71], v[218:221], v[178:181], v[68:71]
	s_waitcnt lgkmcnt(1)
	v_mfma_f32_16x16x32_bf16 v[128:131], v[158:161], v[222:225], v[128:131]
	v_mfma_f32_16x16x32_bf16 v[132:135], v[162:165], v[222:225], v[132:135]
	v_mfma_f32_16x16x32_bf16 v[136:139], v[214:217], v[222:225], v[136:139]
	v_mfma_f32_16x16x32_bf16 v[84:87], v[218:221], v[222:225], v[84:87]
	s_waitcnt lgkmcnt(0)
	v_mfma_f32_16x16x32_bf16 v[100:103], v[158:161], v[226:229], v[100:103]
	v_mfma_f32_16x16x32_bf16 v[140:143], v[162:165], v[226:229], v[140:143]
	v_mfma_f32_16x16x32_bf16 v[150:153], v[214:217], v[226:229], v[150:153]
	v_mfma_f32_16x16x32_bf16 v[154:157], v[218:221], v[226:229], v[154:157]
	s_add_u32 s64, s0, 0x2580
	s_addc_u32 s65, s1, 0
	s_add_u32 s68, s14, 0x2580
	s_waitcnt vmcnt(0)
	s_barrier
	s_addc_u32 s69, s15, 0
	ds_read_b128 v[158:161], v7 offset:32768
	ds_read_b128 v[162:165], v6
	ds_read_b128 v[166:169], v7 offset:34816
	ds_read_b128 v[178:181], v6 offset:2048
	ds_read_b128 v[214:217], v7 offset:36864
	ds_read_b128 v[218:221], v7 offset:38912
	ds_read_b128 v[222:225], v6 offset:4096
	ds_read_b128 v[226:229], v6 offset:6144
	s_waitcnt lgkmcnt(6)
	v_mfma_f32_16x16x32_bf16 v[40:43], v[158:161], v[162:165], v[40:43]
	s_waitcnt lgkmcnt(5)
	v_mfma_f32_16x16x32_bf16 v[44:47], v[166:169], v[162:165], v[44:47]
	s_waitcnt lgkmcnt(4)
	v_mfma_f32_16x16x32_bf16 v[56:59], v[158:161], v[178:181], v[56:59]
	s_mov_b32 m0, s52
	v_mfma_f32_16x16x32_bf16 v[60:63], v[166:169], v[178:181], v[60:63]
	global_load_lds_dwordx4 v0, s[64:65]
	s_waitcnt lgkmcnt(3)
	v_mfma_f32_16x16x32_bf16 v[48:51], v[214:217], v[162:165], v[48:51]
	v_mfma_f32_16x16x32_bf16 v[64:67], v[214:217], v[178:181], v[64:67]
	s_waitcnt lgkmcnt(2)
	v_mfma_f32_16x16x32_bf16 v[174:177], v[218:221], v[162:165], v[174:177]
	ds_read_b128 v[162:165], v6 offset:8192
	v_mfma_f32_16x16x32_bf16 v[170:173], v[218:221], v[178:181], v[170:173]
	ds_read_b128 v[178:181], v6 offset:10240
	s_waitcnt lgkmcnt(3)
	s_mov_b32 m0, s51
	v_mfma_f32_16x16x32_bf16 v[72:75], v[158:161], v[222:225], v[72:75]
	global_load_lds_dwordx4 v0, s[68:69]
	v_mfma_f32_16x16x32_bf16 v[76:79], v[166:169], v[222:225], v[76:79]
	v_mfma_f32_16x16x32_bf16 v[80:83], v[214:217], v[222:225], v[80:83]
	v_mfma_f32_16x16x32_bf16 v[32:35], v[218:221], v[222:225], v[32:35]
	ds_read_b128 v[222:225], v6 offset:12288
	s_waitcnt lgkmcnt(3)
	v_mfma_f32_16x16x32_bf16 v[88:91], v[158:161], v[226:229], v[88:91]
	s_mov_b32 m0, s53
	v_mfma_f32_16x16x32_bf16 v[92:95], v[166:169], v[226:229], v[92:95]
	global_load_lds_dwordx4 v2, s[64:65]
	v_mfma_f32_16x16x32_bf16 v[96:99], v[214:217], v[226:229], v[96:99]
	v_mfma_f32_16x16x32_bf16 v[36:39], v[218:221], v[226:229], v[36:39]
	ds_read_b128 v[226:229], v6 offset:14336
	s_waitcnt lgkmcnt(3)
	v_mfma_f32_16x16x32_bf16 v[104:107], v[158:161], v[162:165], v[104:107]
	s_waitcnt lgkmcnt(2)
	v_mfma_f32_16x16x32_bf16 v[116:119], v[158:161], v[178:181], v[116:119]
	s_waitcnt lgkmcnt(1)
	s_mov_b32 m0, s54
	v_mfma_f32_16x16x32_bf16 v[128:131], v[158:161], v[222:225], v[128:131]
	global_load_lds_dwordx4 v2, s[68:69]
	s_waitcnt lgkmcnt(0)
	v_mfma_f32_16x16x32_bf16 v[100:103], v[158:161], v[226:229], v[100:103]
	ds_read_b128 v[158:161], v7 offset:33792
	v_mfma_f32_16x16x32_bf16 v[108:111], v[166:169], v[162:165], v[108:111]
	v_mfma_f32_16x16x32_bf16 v[120:123], v[166:169], v[178:181], v[120:123]
	v_mfma_f32_16x16x32_bf16 v[132:135], v[166:169], v[222:225], v[132:135]
	s_mov_b32 m0, s55
	v_mfma_f32_16x16x32_bf16 v[140:143], v[166:169], v[226:229], v[140:143]
	global_load_lds_dwordx4 v4, s[64:65]
	ds_read_b128 v[166:169], v6 offset:1024
	v_mfma_f32_16x16x32_bf16 v[112:115], v[214:217], v[162:165], v[112:115]
	v_mfma_f32_16x16x32_bf16 v[52:55], v[218:221], v[162:165], v[52:55]
	ds_read_b128 v[162:165], v7 offset:35840
	v_mfma_f32_16x16x32_bf16 v[124:127], v[214:217], v[178:181], v[124:127]
	v_mfma_f32_16x16x32_bf16 v[68:71], v[218:221], v[178:181], v[68:71]
	ds_read_b128 v[178:181], v6 offset:3072
	s_mov_b32 m0, s58
	v_mfma_f32_16x16x32_bf16 v[136:139], v[214:217], v[222:225], v[136:139]
	global_load_lds_dwordx4 v4, s[68:69]
	v_mfma_f32_16x16x32_bf16 v[84:87], v[218:221], v[222:225], v[84:87]
	ds_read_b128 v[222:225], v6 offset:5120
	v_mfma_f32_16x16x32_bf16 v[150:153], v[214:217], v[226:229], v[150:153]
	ds_read_b128 v[214:217], v7 offset:37888
	v_mfma_f32_16x16x32_bf16 v[154:157], v[218:221], v[226:229], v[154:157]
	ds_read_b128 v[218:221], v7 offset:39936
	ds_read_b128 v[226:229], v6 offset:7168
	s_waitcnt lgkmcnt(6)
	v_mfma_f32_16x16x32_bf16 v[40:43], v[158:161], v[166:169], v[40:43]
	s_waitcnt lgkmcnt(5)
	s_mov_b32 m0, s62
	v_mfma_f32_16x16x32_bf16 v[44:47], v[162:165], v[166:169], v[44:47]
	global_load_lds_dwordx4 v146, s[64:65]
	s_waitcnt lgkmcnt(4)
	v_mfma_f32_16x16x32_bf16 v[56:59], v[158:161], v[178:181], v[56:59]
	v_mfma_f32_16x16x32_bf16 v[60:63], v[162:165], v[178:181], v[60:63]
	s_waitcnt lgkmcnt(3)
	v_mfma_f32_16x16x32_bf16 v[72:75], v[158:161], v[222:225], v[72:75]
	v_mfma_f32_16x16x32_bf16 v[76:79], v[162:165], v[222:225], v[76:79]
	s_waitcnt lgkmcnt(2)
	s_mov_b32 m0, s63
	v_mfma_f32_16x16x32_bf16 v[48:51], v[214:217], v[166:169], v[48:51]
	global_load_lds_dwordx4 v146, s[68:69]
	s_waitcnt lgkmcnt(1)
	v_mfma_f32_16x16x32_bf16 v[174:177], v[218:221], v[166:169], v[174:177]
	ds_read_b128 v[166:169], v6 offset:9216
	v_mfma_f32_16x16x32_bf16 v[64:67], v[214:217], v[178:181], v[64:67]
	v_mfma_f32_16x16x32_bf16 v[170:173], v[218:221], v[178:181], v[170:173]
	ds_read_b128 v[178:181], v6 offset:11264
	v_mfma_f32_16x16x32_bf16 v[80:83], v[214:217], v[222:225], v[80:83]
	v_mfma_f32_16x16x32_bf16 v[32:35], v[218:221], v[222:225], v[32:35]
	ds_read_b128 v[222:225], v6 offset:13312
	s_waitcnt lgkmcnt(3)
	v_mfma_f32_16x16x32_bf16 v[88:91], v[158:161], v[226:229], v[88:91]
	v_mfma_f32_16x16x32_bf16 v[92:95], v[162:165], v[226:229], v[92:95]
	v_mfma_f32_16x16x32_bf16 v[96:99], v[214:217], v[226:229], v[96:99]
	v_mfma_f32_16x16x32_bf16 v[36:39], v[218:221], v[226:229], v[36:39]
	ds_read_b128 v[226:229], v6 offset:15360
	s_waitcnt lgkmcnt(3)
	v_mfma_f32_16x16x32_bf16 v[104:107], v[158:161], v[166:169], v[104:107]
	v_mfma_f32_16x16x32_bf16 v[108:111], v[162:165], v[166:169], v[108:111]
	v_mfma_f32_16x16x32_bf16 v[112:115], v[214:217], v[166:169], v[112:115]
	v_mfma_f32_16x16x32_bf16 v[52:55], v[218:221], v[166:169], v[52:55]
	s_waitcnt lgkmcnt(2)
	v_mfma_f32_16x16x32_bf16 v[116:119], v[158:161], v[178:181], v[116:119]
	v_mfma_f32_16x16x32_bf16 v[120:123], v[162:165], v[178:181], v[120:123]
	v_mfma_f32_16x16x32_bf16 v[124:127], v[214:217], v[178:181], v[124:127]
	v_mfma_f32_16x16x32_bf16 v[68:71], v[218:221], v[178:181], v[68:71]
	s_waitcnt lgkmcnt(1)
	v_mfma_f32_16x16x32_bf16 v[128:131], v[158:161], v[222:225], v[128:131]
	v_mfma_f32_16x16x32_bf16 v[132:135], v[162:165], v[222:225], v[132:135]
	v_mfma_f32_16x16x32_bf16 v[136:139], v[214:217], v[222:225], v[136:139]
	v_mfma_f32_16x16x32_bf16 v[84:87], v[218:221], v[222:225], v[84:87]
	s_waitcnt lgkmcnt(0)
	v_mfma_f32_16x16x32_bf16 v[100:103], v[158:161], v[226:229], v[100:103]
	v_mfma_f32_16x16x32_bf16 v[140:143], v[162:165], v[226:229], v[140:143]
	v_mfma_f32_16x16x32_bf16 v[150:153], v[214:217], v[226:229], v[150:153]
	v_mfma_f32_16x16x32_bf16 v[154:157], v[218:221], v[226:229], v[154:157]
	s_add_u32 s64, s0, 0x2600
	s_addc_u32 s65, s1, 0
	s_add_u32 s68, s14, 0x2600
	s_waitcnt vmcnt(0)
	s_barrier
	s_addc_u32 s69, s15, 0
	ds_read_b128 v[158:161], v8
	ds_read_b128 v[162:165], v12
	ds_read_b128 v[166:169], v9
	ds_read_b128 v[178:181], v13
	ds_read_b128 v[214:217], v11
	ds_read_b128 v[218:221], v10
	ds_read_b128 v[222:225], v14
	ds_read_b128 v[226:229], v15
	s_waitcnt lgkmcnt(6)
	v_mfma_f32_16x16x32_bf16 v[40:43], v[158:161], v[162:165], v[40:43]
	s_waitcnt lgkmcnt(5)
	v_mfma_f32_16x16x32_bf16 v[44:47], v[166:169], v[162:165], v[44:47]
	s_waitcnt lgkmcnt(4)
	v_mfma_f32_16x16x32_bf16 v[56:59], v[158:161], v[178:181], v[56:59]
	s_mov_b32 m0, s42
	v_mfma_f32_16x16x32_bf16 v[60:63], v[166:169], v[178:181], v[60:63]
	global_load_lds_dwordx4 v0, s[64:65]
	s_waitcnt lgkmcnt(3)
	v_mfma_f32_16x16x32_bf16 v[48:51], v[214:217], v[162:165], v[48:51]
	v_mfma_f32_16x16x32_bf16 v[64:67], v[214:217], v[178:181], v[64:67]
	s_waitcnt lgkmcnt(2)
	v_mfma_f32_16x16x32_bf16 v[174:177], v[218:221], v[162:165], v[174:177]
	ds_read_b128 v[162:165], v16
	v_mfma_f32_16x16x32_bf16 v[170:173], v[218:221], v[178:181], v[170:173]
	ds_read_b128 v[178:181], v17
	s_waitcnt lgkmcnt(3)
	s_mov_b32 m0, s43
	v_mfma_f32_16x16x32_bf16 v[72:75], v[158:161], v[222:225], v[72:75]
	global_load_lds_dwordx4 v0, s[68:69]
	v_mfma_f32_16x16x32_bf16 v[76:79], v[166:169], v[222:225], v[76:79]
	v_mfma_f32_16x16x32_bf16 v[80:83], v[214:217], v[222:225], v[80:83]
	v_mfma_f32_16x16x32_bf16 v[32:35], v[218:221], v[222:225], v[32:35]
	ds_read_b128 v[222:225], v18
	s_waitcnt lgkmcnt(3)
	v_mfma_f32_16x16x32_bf16 v[88:91], v[158:161], v[226:229], v[88:91]
	s_mov_b32 m0, s44
	v_mfma_f32_16x16x32_bf16 v[92:95], v[166:169], v[226:229], v[92:95]
	global_load_lds_dwordx4 v2, s[64:65]
	v_mfma_f32_16x16x32_bf16 v[96:99], v[214:217], v[226:229], v[96:99]
	v_mfma_f32_16x16x32_bf16 v[36:39], v[218:221], v[226:229], v[36:39]
	ds_read_b128 v[226:229], v19
	s_waitcnt lgkmcnt(3)
	v_mfma_f32_16x16x32_bf16 v[104:107], v[158:161], v[162:165], v[104:107]
	s_waitcnt lgkmcnt(2)
	v_mfma_f32_16x16x32_bf16 v[116:119], v[158:161], v[178:181], v[116:119]
	s_waitcnt lgkmcnt(1)
	s_mov_b32 m0, s45
	v_mfma_f32_16x16x32_bf16 v[128:131], v[158:161], v[222:225], v[128:131]
	global_load_lds_dwordx4 v2, s[68:69]
	s_waitcnt lgkmcnt(0)
	v_mfma_f32_16x16x32_bf16 v[100:103], v[158:161], v[226:229], v[100:103]
	ds_read_b128 v[158:161], v20
	v_mfma_f32_16x16x32_bf16 v[108:111], v[166:169], v[162:165], v[108:111]
	v_mfma_f32_16x16x32_bf16 v[120:123], v[166:169], v[178:181], v[120:123]
	v_mfma_f32_16x16x32_bf16 v[132:135], v[166:169], v[222:225], v[132:135]
	s_mov_b32 m0, s46
	v_mfma_f32_16x16x32_bf16 v[140:143], v[166:169], v[226:229], v[140:143]
	global_load_lds_dwordx4 v4, s[64:65]
	ds_read_b128 v[166:169], v24
	v_mfma_f32_16x16x32_bf16 v[112:115], v[214:217], v[162:165], v[112:115]
	v_mfma_f32_16x16x32_bf16 v[52:55], v[218:221], v[162:165], v[52:55]
	ds_read_b128 v[162:165], v21
	v_mfma_f32_16x16x32_bf16 v[124:127], v[214:217], v[178:181], v[124:127]
	v_mfma_f32_16x16x32_bf16 v[68:71], v[218:221], v[178:181], v[68:71]
	ds_read_b128 v[178:181], v25
	s_mov_b32 m0, s47
	v_mfma_f32_16x16x32_bf16 v[136:139], v[214:217], v[222:225], v[136:139]
	global_load_lds_dwordx4 v4, s[68:69]
	v_mfma_f32_16x16x32_bf16 v[84:87], v[218:221], v[222:225], v[84:87]
	ds_read_b128 v[222:225], v26
	v_mfma_f32_16x16x32_bf16 v[150:153], v[214:217], v[226:229], v[150:153]
	ds_read_b128 v[214:217], v23
	v_mfma_f32_16x16x32_bf16 v[154:157], v[218:221], v[226:229], v[154:157]
	ds_read_b128 v[218:221], v22
	ds_read_b128 v[226:229], v27
	s_waitcnt lgkmcnt(6)
	v_mfma_f32_16x16x32_bf16 v[40:43], v[158:161], v[166:169], v[40:43]
	s_waitcnt lgkmcnt(5)
	s_mov_b32 m0, s49
	v_mfma_f32_16x16x32_bf16 v[44:47], v[162:165], v[166:169], v[44:47]
	global_load_lds_dwordx4 v146, s[64:65]
	s_waitcnt lgkmcnt(4)
	v_mfma_f32_16x16x32_bf16 v[56:59], v[158:161], v[178:181], v[56:59]
	v_mfma_f32_16x16x32_bf16 v[60:63], v[162:165], v[178:181], v[60:63]
	s_waitcnt lgkmcnt(3)
	v_mfma_f32_16x16x32_bf16 v[72:75], v[158:161], v[222:225], v[72:75]
	v_mfma_f32_16x16x32_bf16 v[76:79], v[162:165], v[222:225], v[76:79]
	s_waitcnt lgkmcnt(2)
	s_mov_b32 m0, s50
	v_mfma_f32_16x16x32_bf16 v[48:51], v[214:217], v[166:169], v[48:51]
	global_load_lds_dwordx4 v146, s[68:69]
	s_waitcnt lgkmcnt(1)
	v_mfma_f32_16x16x32_bf16 v[174:177], v[218:221], v[166:169], v[174:177]
	ds_read_b128 v[166:169], v28
	v_mfma_f32_16x16x32_bf16 v[64:67], v[214:217], v[178:181], v[64:67]
	v_mfma_f32_16x16x32_bf16 v[170:173], v[218:221], v[178:181], v[170:173]
	ds_read_b128 v[178:181], v29
	v_mfma_f32_16x16x32_bf16 v[80:83], v[214:217], v[222:225], v[80:83]
	v_mfma_f32_16x16x32_bf16 v[32:35], v[218:221], v[222:225], v[32:35]
	ds_read_b128 v[222:225], v30
	s_waitcnt lgkmcnt(3)
	v_mfma_f32_16x16x32_bf16 v[88:91], v[158:161], v[226:229], v[88:91]
	v_mfma_f32_16x16x32_bf16 v[92:95], v[162:165], v[226:229], v[92:95]
	v_mfma_f32_16x16x32_bf16 v[96:99], v[214:217], v[226:229], v[96:99]
	v_mfma_f32_16x16x32_bf16 v[36:39], v[218:221], v[226:229], v[36:39]
	ds_read_b128 v[226:229], v31
	s_waitcnt lgkmcnt(3)
	v_mfma_f32_16x16x32_bf16 v[104:107], v[158:161], v[166:169], v[104:107]
	v_mfma_f32_16x16x32_bf16 v[108:111], v[162:165], v[166:169], v[108:111]
	v_mfma_f32_16x16x32_bf16 v[112:115], v[214:217], v[166:169], v[112:115]
	v_mfma_f32_16x16x32_bf16 v[52:55], v[218:221], v[166:169], v[52:55]
	s_waitcnt lgkmcnt(2)
	v_mfma_f32_16x16x32_bf16 v[116:119], v[158:161], v[178:181], v[116:119]
	v_mfma_f32_16x16x32_bf16 v[120:123], v[162:165], v[178:181], v[120:123]
	v_mfma_f32_16x16x32_bf16 v[124:127], v[214:217], v[178:181], v[124:127]
	v_mfma_f32_16x16x32_bf16 v[68:71], v[218:221], v[178:181], v[68:71]
	s_waitcnt lgkmcnt(1)
	v_mfma_f32_16x16x32_bf16 v[128:131], v[158:161], v[222:225], v[128:131]
	v_mfma_f32_16x16x32_bf16 v[132:135], v[162:165], v[222:225], v[132:135]
	v_mfma_f32_16x16x32_bf16 v[136:139], v[214:217], v[222:225], v[136:139]
	v_mfma_f32_16x16x32_bf16 v[84:87], v[218:221], v[222:225], v[84:87]
	s_waitcnt lgkmcnt(0)
	v_mfma_f32_16x16x32_bf16 v[100:103], v[158:161], v[226:229], v[100:103]
	v_mfma_f32_16x16x32_bf16 v[140:143], v[162:165], v[226:229], v[140:143]
	v_mfma_f32_16x16x32_bf16 v[150:153], v[214:217], v[226:229], v[150:153]
	v_mfma_f32_16x16x32_bf16 v[154:157], v[218:221], v[226:229], v[154:157]
	s_add_u32 s64, s0, 0x2680
	s_addc_u32 s65, s1, 0
	s_add_u32 s68, s14, 0x2680
	s_waitcnt vmcnt(0)
	s_barrier
	s_addc_u32 s69, s15, 0
	ds_read_b128 v[158:161], v7 offset:32768
	ds_read_b128 v[162:165], v6
	ds_read_b128 v[166:169], v7 offset:34816
	ds_read_b128 v[178:181], v6 offset:2048
	ds_read_b128 v[214:217], v7 offset:36864
	ds_read_b128 v[218:221], v7 offset:38912
	ds_read_b128 v[222:225], v6 offset:4096
	ds_read_b128 v[226:229], v6 offset:6144
	s_waitcnt lgkmcnt(6)
	v_mfma_f32_16x16x32_bf16 v[40:43], v[158:161], v[162:165], v[40:43]
	s_waitcnt lgkmcnt(5)
	v_mfma_f32_16x16x32_bf16 v[44:47], v[166:169], v[162:165], v[44:47]
	s_waitcnt lgkmcnt(4)
	v_mfma_f32_16x16x32_bf16 v[56:59], v[158:161], v[178:181], v[56:59]
	s_mov_b32 m0, s52
	v_mfma_f32_16x16x32_bf16 v[60:63], v[166:169], v[178:181], v[60:63]
	global_load_lds_dwordx4 v0, s[64:65]
	s_waitcnt lgkmcnt(3)
	v_mfma_f32_16x16x32_bf16 v[48:51], v[214:217], v[162:165], v[48:51]
	v_mfma_f32_16x16x32_bf16 v[64:67], v[214:217], v[178:181], v[64:67]
	s_waitcnt lgkmcnt(2)
	v_mfma_f32_16x16x32_bf16 v[174:177], v[218:221], v[162:165], v[174:177]
	ds_read_b128 v[162:165], v6 offset:8192
	v_mfma_f32_16x16x32_bf16 v[170:173], v[218:221], v[178:181], v[170:173]
	ds_read_b128 v[178:181], v6 offset:10240
	s_waitcnt lgkmcnt(3)
	s_mov_b32 m0, s51
	v_mfma_f32_16x16x32_bf16 v[72:75], v[158:161], v[222:225], v[72:75]
	global_load_lds_dwordx4 v0, s[68:69]
	v_mfma_f32_16x16x32_bf16 v[76:79], v[166:169], v[222:225], v[76:79]
	v_mfma_f32_16x16x32_bf16 v[80:83], v[214:217], v[222:225], v[80:83]
	v_mfma_f32_16x16x32_bf16 v[32:35], v[218:221], v[222:225], v[32:35]
	ds_read_b128 v[222:225], v6 offset:12288
	s_waitcnt lgkmcnt(3)
	v_mfma_f32_16x16x32_bf16 v[88:91], v[158:161], v[226:229], v[88:91]
	s_mov_b32 m0, s53
	v_mfma_f32_16x16x32_bf16 v[92:95], v[166:169], v[226:229], v[92:95]
	global_load_lds_dwordx4 v2, s[64:65]
	v_mfma_f32_16x16x32_bf16 v[96:99], v[214:217], v[226:229], v[96:99]
	v_mfma_f32_16x16x32_bf16 v[36:39], v[218:221], v[226:229], v[36:39]
	ds_read_b128 v[226:229], v6 offset:14336
	s_waitcnt lgkmcnt(3)
	v_mfma_f32_16x16x32_bf16 v[104:107], v[158:161], v[162:165], v[104:107]
	s_waitcnt lgkmcnt(2)
	v_mfma_f32_16x16x32_bf16 v[116:119], v[158:161], v[178:181], v[116:119]
	s_waitcnt lgkmcnt(1)
	s_mov_b32 m0, s54
	v_mfma_f32_16x16x32_bf16 v[128:131], v[158:161], v[222:225], v[128:131]
	global_load_lds_dwordx4 v2, s[68:69]
	s_waitcnt lgkmcnt(0)
	v_mfma_f32_16x16x32_bf16 v[100:103], v[158:161], v[226:229], v[100:103]
	ds_read_b128 v[158:161], v7 offset:33792
	v_mfma_f32_16x16x32_bf16 v[108:111], v[166:169], v[162:165], v[108:111]
	v_mfma_f32_16x16x32_bf16 v[120:123], v[166:169], v[178:181], v[120:123]
	v_mfma_f32_16x16x32_bf16 v[132:135], v[166:169], v[222:225], v[132:135]
	s_mov_b32 m0, s55
	v_mfma_f32_16x16x32_bf16 v[140:143], v[166:169], v[226:229], v[140:143]
	global_load_lds_dwordx4 v4, s[64:65]
	ds_read_b128 v[166:169], v6 offset:1024
	v_mfma_f32_16x16x32_bf16 v[112:115], v[214:217], v[162:165], v[112:115]
	v_mfma_f32_16x16x32_bf16 v[52:55], v[218:221], v[162:165], v[52:55]
	ds_read_b128 v[162:165], v7 offset:35840
	v_mfma_f32_16x16x32_bf16 v[124:127], v[214:217], v[178:181], v[124:127]
	v_mfma_f32_16x16x32_bf16 v[68:71], v[218:221], v[178:181], v[68:71]
	ds_read_b128 v[178:181], v6 offset:3072
	s_mov_b32 m0, s58
	v_mfma_f32_16x16x32_bf16 v[136:139], v[214:217], v[222:225], v[136:139]
	global_load_lds_dwordx4 v4, s[68:69]
	v_mfma_f32_16x16x32_bf16 v[84:87], v[218:221], v[222:225], v[84:87]
	ds_read_b128 v[222:225], v6 offset:5120
	v_mfma_f32_16x16x32_bf16 v[150:153], v[214:217], v[226:229], v[150:153]
	ds_read_b128 v[214:217], v7 offset:37888
	v_mfma_f32_16x16x32_bf16 v[154:157], v[218:221], v[226:229], v[154:157]
	ds_read_b128 v[218:221], v7 offset:39936
	ds_read_b128 v[226:229], v6 offset:7168
	s_waitcnt lgkmcnt(6)
	v_mfma_f32_16x16x32_bf16 v[40:43], v[158:161], v[166:169], v[40:43]
	s_waitcnt lgkmcnt(5)
	s_mov_b32 m0, s62
	v_mfma_f32_16x16x32_bf16 v[44:47], v[162:165], v[166:169], v[44:47]
	global_load_lds_dwordx4 v146, s[64:65]
	s_waitcnt lgkmcnt(4)
	v_mfma_f32_16x16x32_bf16 v[56:59], v[158:161], v[178:181], v[56:59]
	v_mfma_f32_16x16x32_bf16 v[60:63], v[162:165], v[178:181], v[60:63]
	s_waitcnt lgkmcnt(3)
	v_mfma_f32_16x16x32_bf16 v[72:75], v[158:161], v[222:225], v[72:75]
	v_mfma_f32_16x16x32_bf16 v[76:79], v[162:165], v[222:225], v[76:79]
	s_waitcnt lgkmcnt(2)
	s_mov_b32 m0, s63
	v_mfma_f32_16x16x32_bf16 v[48:51], v[214:217], v[166:169], v[48:51]
	global_load_lds_dwordx4 v146, s[68:69]
	s_waitcnt lgkmcnt(1)
	v_mfma_f32_16x16x32_bf16 v[174:177], v[218:221], v[166:169], v[174:177]
	ds_read_b128 v[166:169], v6 offset:9216
	v_mfma_f32_16x16x32_bf16 v[64:67], v[214:217], v[178:181], v[64:67]
	v_mfma_f32_16x16x32_bf16 v[170:173], v[218:221], v[178:181], v[170:173]
	ds_read_b128 v[178:181], v6 offset:11264
	v_mfma_f32_16x16x32_bf16 v[80:83], v[214:217], v[222:225], v[80:83]
	v_mfma_f32_16x16x32_bf16 v[32:35], v[218:221], v[222:225], v[32:35]
	ds_read_b128 v[222:225], v6 offset:13312
	s_waitcnt lgkmcnt(3)
	v_mfma_f32_16x16x32_bf16 v[88:91], v[158:161], v[226:229], v[88:91]
	v_mfma_f32_16x16x32_bf16 v[92:95], v[162:165], v[226:229], v[92:95]
	v_mfma_f32_16x16x32_bf16 v[96:99], v[214:217], v[226:229], v[96:99]
	v_mfma_f32_16x16x32_bf16 v[36:39], v[218:221], v[226:229], v[36:39]
	ds_read_b128 v[226:229], v6 offset:15360
	s_waitcnt lgkmcnt(3)
	v_mfma_f32_16x16x32_bf16 v[104:107], v[158:161], v[166:169], v[104:107]
	v_mfma_f32_16x16x32_bf16 v[108:111], v[162:165], v[166:169], v[108:111]
	v_mfma_f32_16x16x32_bf16 v[112:115], v[214:217], v[166:169], v[112:115]
	v_mfma_f32_16x16x32_bf16 v[52:55], v[218:221], v[166:169], v[52:55]
	s_waitcnt lgkmcnt(2)
	v_mfma_f32_16x16x32_bf16 v[116:119], v[158:161], v[178:181], v[116:119]
	v_mfma_f32_16x16x32_bf16 v[120:123], v[162:165], v[178:181], v[120:123]
	v_mfma_f32_16x16x32_bf16 v[124:127], v[214:217], v[178:181], v[124:127]
	v_mfma_f32_16x16x32_bf16 v[68:71], v[218:221], v[178:181], v[68:71]
	s_waitcnt lgkmcnt(1)
	v_mfma_f32_16x16x32_bf16 v[128:131], v[158:161], v[222:225], v[128:131]
	v_mfma_f32_16x16x32_bf16 v[132:135], v[162:165], v[222:225], v[132:135]
	v_mfma_f32_16x16x32_bf16 v[136:139], v[214:217], v[222:225], v[136:139]
	v_mfma_f32_16x16x32_bf16 v[84:87], v[218:221], v[222:225], v[84:87]
	s_waitcnt lgkmcnt(0)
	v_mfma_f32_16x16x32_bf16 v[100:103], v[158:161], v[226:229], v[100:103]
	v_mfma_f32_16x16x32_bf16 v[140:143], v[162:165], v[226:229], v[140:143]
	v_mfma_f32_16x16x32_bf16 v[150:153], v[214:217], v[226:229], v[150:153]
	v_mfma_f32_16x16x32_bf16 v[154:157], v[218:221], v[226:229], v[154:157]
	s_add_u32 s64, s0, 0x2700
	s_addc_u32 s65, s1, 0
	s_add_u32 s68, s14, 0x2700
	s_waitcnt vmcnt(0)
	s_barrier
	s_addc_u32 s69, s15, 0
	ds_read_b128 v[158:161], v8
	ds_read_b128 v[162:165], v12
	ds_read_b128 v[166:169], v9
	ds_read_b128 v[178:181], v13
	ds_read_b128 v[214:217], v11
	ds_read_b128 v[218:221], v10
	ds_read_b128 v[222:225], v14
	ds_read_b128 v[226:229], v15
	s_waitcnt lgkmcnt(6)
	v_mfma_f32_16x16x32_bf16 v[40:43], v[158:161], v[162:165], v[40:43]
	s_waitcnt lgkmcnt(5)
	v_mfma_f32_16x16x32_bf16 v[44:47], v[166:169], v[162:165], v[44:47]
	s_waitcnt lgkmcnt(4)
	v_mfma_f32_16x16x32_bf16 v[56:59], v[158:161], v[178:181], v[56:59]
	s_mov_b32 m0, s42
	v_mfma_f32_16x16x32_bf16 v[60:63], v[166:169], v[178:181], v[60:63]
	global_load_lds_dwordx4 v0, s[64:65]
	s_waitcnt lgkmcnt(3)
	v_mfma_f32_16x16x32_bf16 v[48:51], v[214:217], v[162:165], v[48:51]
	v_mfma_f32_16x16x32_bf16 v[64:67], v[214:217], v[178:181], v[64:67]
	s_waitcnt lgkmcnt(2)
	v_mfma_f32_16x16x32_bf16 v[174:177], v[218:221], v[162:165], v[174:177]
	ds_read_b128 v[162:165], v16
	v_mfma_f32_16x16x32_bf16 v[170:173], v[218:221], v[178:181], v[170:173]
	ds_read_b128 v[178:181], v17
	s_waitcnt lgkmcnt(3)
	s_mov_b32 m0, s43
	v_mfma_f32_16x16x32_bf16 v[72:75], v[158:161], v[222:225], v[72:75]
	global_load_lds_dwordx4 v0, s[68:69]
	v_mfma_f32_16x16x32_bf16 v[76:79], v[166:169], v[222:225], v[76:79]
	v_mfma_f32_16x16x32_bf16 v[80:83], v[214:217], v[222:225], v[80:83]
	v_mfma_f32_16x16x32_bf16 v[32:35], v[218:221], v[222:225], v[32:35]
	ds_read_b128 v[222:225], v18
	s_waitcnt lgkmcnt(3)
	v_mfma_f32_16x16x32_bf16 v[88:91], v[158:161], v[226:229], v[88:91]
	s_mov_b32 m0, s44
	v_mfma_f32_16x16x32_bf16 v[92:95], v[166:169], v[226:229], v[92:95]
	global_load_lds_dwordx4 v2, s[64:65]
	v_mfma_f32_16x16x32_bf16 v[96:99], v[214:217], v[226:229], v[96:99]
	v_mfma_f32_16x16x32_bf16 v[36:39], v[218:221], v[226:229], v[36:39]
	ds_read_b128 v[226:229], v19
	s_waitcnt lgkmcnt(3)
	v_mfma_f32_16x16x32_bf16 v[104:107], v[158:161], v[162:165], v[104:107]
	s_waitcnt lgkmcnt(2)
	v_mfma_f32_16x16x32_bf16 v[116:119], v[158:161], v[178:181], v[116:119]
	s_waitcnt lgkmcnt(1)
	s_mov_b32 m0, s45
	v_mfma_f32_16x16x32_bf16 v[128:131], v[158:161], v[222:225], v[128:131]
	global_load_lds_dwordx4 v2, s[68:69]
	s_waitcnt lgkmcnt(0)
	v_mfma_f32_16x16x32_bf16 v[100:103], v[158:161], v[226:229], v[100:103]
	ds_read_b128 v[158:161], v20
	v_mfma_f32_16x16x32_bf16 v[108:111], v[166:169], v[162:165], v[108:111]
	v_mfma_f32_16x16x32_bf16 v[120:123], v[166:169], v[178:181], v[120:123]
	v_mfma_f32_16x16x32_bf16 v[132:135], v[166:169], v[222:225], v[132:135]
	s_mov_b32 m0, s46
	v_mfma_f32_16x16x32_bf16 v[140:143], v[166:169], v[226:229], v[140:143]
	global_load_lds_dwordx4 v4, s[64:65]
	ds_read_b128 v[166:169], v24
	v_mfma_f32_16x16x32_bf16 v[112:115], v[214:217], v[162:165], v[112:115]
	v_mfma_f32_16x16x32_bf16 v[52:55], v[218:221], v[162:165], v[52:55]
	ds_read_b128 v[162:165], v21
	v_mfma_f32_16x16x32_bf16 v[124:127], v[214:217], v[178:181], v[124:127]
	v_mfma_f32_16x16x32_bf16 v[68:71], v[218:221], v[178:181], v[68:71]
	ds_read_b128 v[178:181], v25
	s_mov_b32 m0, s47
	v_mfma_f32_16x16x32_bf16 v[136:139], v[214:217], v[222:225], v[136:139]
	global_load_lds_dwordx4 v4, s[68:69]
	v_mfma_f32_16x16x32_bf16 v[84:87], v[218:221], v[222:225], v[84:87]
	ds_read_b128 v[222:225], v26
	v_mfma_f32_16x16x32_bf16 v[150:153], v[214:217], v[226:229], v[150:153]
	ds_read_b128 v[214:217], v23
	v_mfma_f32_16x16x32_bf16 v[154:157], v[218:221], v[226:229], v[154:157]
	ds_read_b128 v[218:221], v22
	ds_read_b128 v[226:229], v27
	s_waitcnt lgkmcnt(6)
	v_mfma_f32_16x16x32_bf16 v[40:43], v[158:161], v[166:169], v[40:43]
	s_waitcnt lgkmcnt(5)
	s_mov_b32 m0, s49
	v_mfma_f32_16x16x32_bf16 v[44:47], v[162:165], v[166:169], v[44:47]
	global_load_lds_dwordx4 v146, s[64:65]
	s_waitcnt lgkmcnt(4)
	v_mfma_f32_16x16x32_bf16 v[56:59], v[158:161], v[178:181], v[56:59]
	v_mfma_f32_16x16x32_bf16 v[60:63], v[162:165], v[178:181], v[60:63]
	s_waitcnt lgkmcnt(3)
	v_mfma_f32_16x16x32_bf16 v[72:75], v[158:161], v[222:225], v[72:75]
	v_mfma_f32_16x16x32_bf16 v[76:79], v[162:165], v[222:225], v[76:79]
	s_waitcnt lgkmcnt(2)
	s_mov_b32 m0, s50
	v_mfma_f32_16x16x32_bf16 v[48:51], v[214:217], v[166:169], v[48:51]
	global_load_lds_dwordx4 v146, s[68:69]
	s_waitcnt lgkmcnt(1)
	v_mfma_f32_16x16x32_bf16 v[174:177], v[218:221], v[166:169], v[174:177]
	ds_read_b128 v[166:169], v28
	v_mfma_f32_16x16x32_bf16 v[64:67], v[214:217], v[178:181], v[64:67]
	v_mfma_f32_16x16x32_bf16 v[170:173], v[218:221], v[178:181], v[170:173]
	ds_read_b128 v[178:181], v29
	v_mfma_f32_16x16x32_bf16 v[80:83], v[214:217], v[222:225], v[80:83]
	v_mfma_f32_16x16x32_bf16 v[32:35], v[218:221], v[222:225], v[32:35]
	ds_read_b128 v[222:225], v30
	s_waitcnt lgkmcnt(3)
	v_mfma_f32_16x16x32_bf16 v[88:91], v[158:161], v[226:229], v[88:91]
	v_mfma_f32_16x16x32_bf16 v[92:95], v[162:165], v[226:229], v[92:95]
	v_mfma_f32_16x16x32_bf16 v[96:99], v[214:217], v[226:229], v[96:99]
	v_mfma_f32_16x16x32_bf16 v[36:39], v[218:221], v[226:229], v[36:39]
	ds_read_b128 v[226:229], v31
	s_waitcnt lgkmcnt(3)
	v_mfma_f32_16x16x32_bf16 v[104:107], v[158:161], v[166:169], v[104:107]
	v_mfma_f32_16x16x32_bf16 v[108:111], v[162:165], v[166:169], v[108:111]
	v_mfma_f32_16x16x32_bf16 v[112:115], v[214:217], v[166:169], v[112:115]
	v_mfma_f32_16x16x32_bf16 v[52:55], v[218:221], v[166:169], v[52:55]
	s_waitcnt lgkmcnt(2)
	v_mfma_f32_16x16x32_bf16 v[116:119], v[158:161], v[178:181], v[116:119]
	v_mfma_f32_16x16x32_bf16 v[120:123], v[162:165], v[178:181], v[120:123]
	v_mfma_f32_16x16x32_bf16 v[124:127], v[214:217], v[178:181], v[124:127]
	v_mfma_f32_16x16x32_bf16 v[68:71], v[218:221], v[178:181], v[68:71]
	s_waitcnt lgkmcnt(1)
	v_mfma_f32_16x16x32_bf16 v[128:131], v[158:161], v[222:225], v[128:131]
	v_mfma_f32_16x16x32_bf16 v[132:135], v[162:165], v[222:225], v[132:135]
	v_mfma_f32_16x16x32_bf16 v[136:139], v[214:217], v[222:225], v[136:139]
	v_mfma_f32_16x16x32_bf16 v[84:87], v[218:221], v[222:225], v[84:87]
	s_waitcnt lgkmcnt(0)
	v_mfma_f32_16x16x32_bf16 v[100:103], v[158:161], v[226:229], v[100:103]
	v_mfma_f32_16x16x32_bf16 v[140:143], v[162:165], v[226:229], v[140:143]
	v_mfma_f32_16x16x32_bf16 v[150:153], v[214:217], v[226:229], v[150:153]
	v_mfma_f32_16x16x32_bf16 v[154:157], v[218:221], v[226:229], v[154:157]
	s_add_u32 s64, s0, 0x2780
	s_addc_u32 s65, s1, 0
	s_add_u32 s68, s14, 0x2780
	s_waitcnt vmcnt(0)
	s_barrier
	s_addc_u32 s69, s15, 0
	ds_read_b128 v[158:161], v7 offset:32768
	ds_read_b128 v[162:165], v6
	ds_read_b128 v[166:169], v7 offset:34816
	ds_read_b128 v[178:181], v6 offset:2048
	ds_read_b128 v[214:217], v7 offset:36864
	ds_read_b128 v[218:221], v7 offset:38912
	ds_read_b128 v[222:225], v6 offset:4096
	ds_read_b128 v[226:229], v6 offset:6144
	s_waitcnt lgkmcnt(6)
	v_mfma_f32_16x16x32_bf16 v[40:43], v[158:161], v[162:165], v[40:43]
	s_waitcnt lgkmcnt(5)
	v_mfma_f32_16x16x32_bf16 v[44:47], v[166:169], v[162:165], v[44:47]
	s_waitcnt lgkmcnt(4)
	v_mfma_f32_16x16x32_bf16 v[56:59], v[158:161], v[178:181], v[56:59]
	s_mov_b32 m0, s52
	v_mfma_f32_16x16x32_bf16 v[60:63], v[166:169], v[178:181], v[60:63]
	global_load_lds_dwordx4 v0, s[64:65]
	s_waitcnt lgkmcnt(3)
	v_mfma_f32_16x16x32_bf16 v[48:51], v[214:217], v[162:165], v[48:51]
	v_mfma_f32_16x16x32_bf16 v[64:67], v[214:217], v[178:181], v[64:67]
	s_waitcnt lgkmcnt(2)
	v_mfma_f32_16x16x32_bf16 v[174:177], v[218:221], v[162:165], v[174:177]
	ds_read_b128 v[162:165], v6 offset:8192
	v_mfma_f32_16x16x32_bf16 v[170:173], v[218:221], v[178:181], v[170:173]
	ds_read_b128 v[178:181], v6 offset:10240
	s_waitcnt lgkmcnt(3)
	s_mov_b32 m0, s51
	v_mfma_f32_16x16x32_bf16 v[72:75], v[158:161], v[222:225], v[72:75]
	global_load_lds_dwordx4 v0, s[68:69]
	v_mfma_f32_16x16x32_bf16 v[76:79], v[166:169], v[222:225], v[76:79]
	v_mfma_f32_16x16x32_bf16 v[80:83], v[214:217], v[222:225], v[80:83]
	v_mfma_f32_16x16x32_bf16 v[32:35], v[218:221], v[222:225], v[32:35]
	ds_read_b128 v[222:225], v6 offset:12288
	s_waitcnt lgkmcnt(3)
	v_mfma_f32_16x16x32_bf16 v[88:91], v[158:161], v[226:229], v[88:91]
	s_mov_b32 m0, s53
	v_mfma_f32_16x16x32_bf16 v[92:95], v[166:169], v[226:229], v[92:95]
	global_load_lds_dwordx4 v2, s[64:65]
	v_mfma_f32_16x16x32_bf16 v[96:99], v[214:217], v[226:229], v[96:99]
	v_mfma_f32_16x16x32_bf16 v[36:39], v[218:221], v[226:229], v[36:39]
	ds_read_b128 v[226:229], v6 offset:14336
	s_waitcnt lgkmcnt(3)
	v_mfma_f32_16x16x32_bf16 v[104:107], v[158:161], v[162:165], v[104:107]
	s_waitcnt lgkmcnt(2)
	v_mfma_f32_16x16x32_bf16 v[116:119], v[158:161], v[178:181], v[116:119]
	s_waitcnt lgkmcnt(1)
	s_mov_b32 m0, s54
	v_mfma_f32_16x16x32_bf16 v[128:131], v[158:161], v[222:225], v[128:131]
	global_load_lds_dwordx4 v2, s[68:69]
	s_waitcnt lgkmcnt(0)
	v_mfma_f32_16x16x32_bf16 v[100:103], v[158:161], v[226:229], v[100:103]
	ds_read_b128 v[158:161], v7 offset:33792
	v_mfma_f32_16x16x32_bf16 v[108:111], v[166:169], v[162:165], v[108:111]
	v_mfma_f32_16x16x32_bf16 v[120:123], v[166:169], v[178:181], v[120:123]
	v_mfma_f32_16x16x32_bf16 v[132:135], v[166:169], v[222:225], v[132:135]
	s_mov_b32 m0, s55
	v_mfma_f32_16x16x32_bf16 v[140:143], v[166:169], v[226:229], v[140:143]
	global_load_lds_dwordx4 v4, s[64:65]
	ds_read_b128 v[166:169], v6 offset:1024
	v_mfma_f32_16x16x32_bf16 v[112:115], v[214:217], v[162:165], v[112:115]
	v_mfma_f32_16x16x32_bf16 v[52:55], v[218:221], v[162:165], v[52:55]
	ds_read_b128 v[162:165], v7 offset:35840
	v_mfma_f32_16x16x32_bf16 v[124:127], v[214:217], v[178:181], v[124:127]
	v_mfma_f32_16x16x32_bf16 v[68:71], v[218:221], v[178:181], v[68:71]
	ds_read_b128 v[178:181], v6 offset:3072
	s_mov_b32 m0, s58
	v_mfma_f32_16x16x32_bf16 v[136:139], v[214:217], v[222:225], v[136:139]
	global_load_lds_dwordx4 v4, s[68:69]
	v_mfma_f32_16x16x32_bf16 v[84:87], v[218:221], v[222:225], v[84:87]
	ds_read_b128 v[222:225], v6 offset:5120
	v_mfma_f32_16x16x32_bf16 v[150:153], v[214:217], v[226:229], v[150:153]
	ds_read_b128 v[214:217], v7 offset:37888
	v_mfma_f32_16x16x32_bf16 v[154:157], v[218:221], v[226:229], v[154:157]
	ds_read_b128 v[218:221], v7 offset:39936
	ds_read_b128 v[226:229], v6 offset:7168
	s_waitcnt lgkmcnt(6)
	v_mfma_f32_16x16x32_bf16 v[40:43], v[158:161], v[166:169], v[40:43]
	s_waitcnt lgkmcnt(5)
	s_mov_b32 m0, s62
	v_mfma_f32_16x16x32_bf16 v[44:47], v[162:165], v[166:169], v[44:47]
	global_load_lds_dwordx4 v146, s[64:65]
	s_waitcnt lgkmcnt(4)
	v_mfma_f32_16x16x32_bf16 v[56:59], v[158:161], v[178:181], v[56:59]
	v_mfma_f32_16x16x32_bf16 v[60:63], v[162:165], v[178:181], v[60:63]
	s_waitcnt lgkmcnt(3)
	v_mfma_f32_16x16x32_bf16 v[72:75], v[158:161], v[222:225], v[72:75]
	v_mfma_f32_16x16x32_bf16 v[76:79], v[162:165], v[222:225], v[76:79]
	s_waitcnt lgkmcnt(2)
	s_mov_b32 m0, s63
	v_mfma_f32_16x16x32_bf16 v[48:51], v[214:217], v[166:169], v[48:51]
	global_load_lds_dwordx4 v146, s[68:69]
	s_waitcnt lgkmcnt(1)
	v_mfma_f32_16x16x32_bf16 v[174:177], v[218:221], v[166:169], v[174:177]
	ds_read_b128 v[166:169], v6 offset:9216
	v_mfma_f32_16x16x32_bf16 v[64:67], v[214:217], v[178:181], v[64:67]
	v_mfma_f32_16x16x32_bf16 v[170:173], v[218:221], v[178:181], v[170:173]
	ds_read_b128 v[178:181], v6 offset:11264
	v_mfma_f32_16x16x32_bf16 v[80:83], v[214:217], v[222:225], v[80:83]
	v_mfma_f32_16x16x32_bf16 v[32:35], v[218:221], v[222:225], v[32:35]
	ds_read_b128 v[222:225], v6 offset:13312
	s_waitcnt lgkmcnt(3)
	v_mfma_f32_16x16x32_bf16 v[88:91], v[158:161], v[226:229], v[88:91]
	v_mfma_f32_16x16x32_bf16 v[92:95], v[162:165], v[226:229], v[92:95]
	v_mfma_f32_16x16x32_bf16 v[96:99], v[214:217], v[226:229], v[96:99]
	v_mfma_f32_16x16x32_bf16 v[36:39], v[218:221], v[226:229], v[36:39]
	ds_read_b128 v[226:229], v6 offset:15360
	s_waitcnt lgkmcnt(3)
	v_mfma_f32_16x16x32_bf16 v[104:107], v[158:161], v[166:169], v[104:107]
	v_mfma_f32_16x16x32_bf16 v[108:111], v[162:165], v[166:169], v[108:111]
	v_mfma_f32_16x16x32_bf16 v[112:115], v[214:217], v[166:169], v[112:115]
	v_mfma_f32_16x16x32_bf16 v[52:55], v[218:221], v[166:169], v[52:55]
	s_waitcnt lgkmcnt(2)
	v_mfma_f32_16x16x32_bf16 v[116:119], v[158:161], v[178:181], v[116:119]
	v_mfma_f32_16x16x32_bf16 v[120:123], v[162:165], v[178:181], v[120:123]
	v_mfma_f32_16x16x32_bf16 v[124:127], v[214:217], v[178:181], v[124:127]
	v_mfma_f32_16x16x32_bf16 v[68:71], v[218:221], v[178:181], v[68:71]
	s_waitcnt lgkmcnt(1)
	v_mfma_f32_16x16x32_bf16 v[128:131], v[158:161], v[222:225], v[128:131]
	v_mfma_f32_16x16x32_bf16 v[132:135], v[162:165], v[222:225], v[132:135]
	v_mfma_f32_16x16x32_bf16 v[136:139], v[214:217], v[222:225], v[136:139]
	v_mfma_f32_16x16x32_bf16 v[84:87], v[218:221], v[222:225], v[84:87]
	s_waitcnt lgkmcnt(0)
	v_mfma_f32_16x16x32_bf16 v[100:103], v[158:161], v[226:229], v[100:103]
	v_mfma_f32_16x16x32_bf16 v[140:143], v[162:165], v[226:229], v[140:143]
	v_mfma_f32_16x16x32_bf16 v[150:153], v[214:217], v[226:229], v[150:153]
	v_mfma_f32_16x16x32_bf16 v[154:157], v[218:221], v[226:229], v[154:157]
	s_add_u32 s64, s0, 0x2800
	s_addc_u32 s65, s1, 0
	s_add_u32 s68, s14, 0x2800
	s_waitcnt vmcnt(0)
	s_barrier
	s_addc_u32 s69, s15, 0
	ds_read_b128 v[158:161], v8
	ds_read_b128 v[162:165], v12
	ds_read_b128 v[166:169], v9
	ds_read_b128 v[178:181], v13
	ds_read_b128 v[214:217], v11
	ds_read_b128 v[218:221], v10
	ds_read_b128 v[222:225], v14
	ds_read_b128 v[226:229], v15
	s_waitcnt lgkmcnt(6)
	v_mfma_f32_16x16x32_bf16 v[40:43], v[158:161], v[162:165], v[40:43]
	s_waitcnt lgkmcnt(5)
	v_mfma_f32_16x16x32_bf16 v[44:47], v[166:169], v[162:165], v[44:47]
	s_waitcnt lgkmcnt(4)
	v_mfma_f32_16x16x32_bf16 v[56:59], v[158:161], v[178:181], v[56:59]
	s_mov_b32 m0, s42
	v_mfma_f32_16x16x32_bf16 v[60:63], v[166:169], v[178:181], v[60:63]
	global_load_lds_dwordx4 v0, s[64:65]
	s_waitcnt lgkmcnt(3)
	v_mfma_f32_16x16x32_bf16 v[48:51], v[214:217], v[162:165], v[48:51]
	v_mfma_f32_16x16x32_bf16 v[64:67], v[214:217], v[178:181], v[64:67]
	s_waitcnt lgkmcnt(2)
	v_mfma_f32_16x16x32_bf16 v[174:177], v[218:221], v[162:165], v[174:177]
	ds_read_b128 v[162:165], v16
	v_mfma_f32_16x16x32_bf16 v[170:173], v[218:221], v[178:181], v[170:173]
	ds_read_b128 v[178:181], v17
	s_waitcnt lgkmcnt(3)
	s_mov_b32 m0, s43
	v_mfma_f32_16x16x32_bf16 v[72:75], v[158:161], v[222:225], v[72:75]
	global_load_lds_dwordx4 v0, s[68:69]
	v_mfma_f32_16x16x32_bf16 v[76:79], v[166:169], v[222:225], v[76:79]
	v_mfma_f32_16x16x32_bf16 v[80:83], v[214:217], v[222:225], v[80:83]
	v_mfma_f32_16x16x32_bf16 v[32:35], v[218:221], v[222:225], v[32:35]
	ds_read_b128 v[222:225], v18
	s_waitcnt lgkmcnt(3)
	v_mfma_f32_16x16x32_bf16 v[88:91], v[158:161], v[226:229], v[88:91]
	s_mov_b32 m0, s44
	v_mfma_f32_16x16x32_bf16 v[92:95], v[166:169], v[226:229], v[92:95]
	global_load_lds_dwordx4 v2, s[64:65]
	v_mfma_f32_16x16x32_bf16 v[96:99], v[214:217], v[226:229], v[96:99]
	v_mfma_f32_16x16x32_bf16 v[36:39], v[218:221], v[226:229], v[36:39]
	ds_read_b128 v[226:229], v19
	s_waitcnt lgkmcnt(3)
	v_mfma_f32_16x16x32_bf16 v[104:107], v[158:161], v[162:165], v[104:107]
	s_waitcnt lgkmcnt(2)
	v_mfma_f32_16x16x32_bf16 v[116:119], v[158:161], v[178:181], v[116:119]
	s_waitcnt lgkmcnt(1)
	s_mov_b32 m0, s45
	v_mfma_f32_16x16x32_bf16 v[128:131], v[158:161], v[222:225], v[128:131]
	global_load_lds_dwordx4 v2, s[68:69]
	s_waitcnt lgkmcnt(0)
	v_mfma_f32_16x16x32_bf16 v[100:103], v[158:161], v[226:229], v[100:103]
	ds_read_b128 v[158:161], v20
	v_mfma_f32_16x16x32_bf16 v[108:111], v[166:169], v[162:165], v[108:111]
	v_mfma_f32_16x16x32_bf16 v[120:123], v[166:169], v[178:181], v[120:123]
	v_mfma_f32_16x16x32_bf16 v[132:135], v[166:169], v[222:225], v[132:135]
	s_mov_b32 m0, s46
	v_mfma_f32_16x16x32_bf16 v[140:143], v[166:169], v[226:229], v[140:143]
	global_load_lds_dwordx4 v4, s[64:65]
	ds_read_b128 v[166:169], v24
	v_mfma_f32_16x16x32_bf16 v[112:115], v[214:217], v[162:165], v[112:115]
	v_mfma_f32_16x16x32_bf16 v[52:55], v[218:221], v[162:165], v[52:55]
	ds_read_b128 v[162:165], v21
	v_mfma_f32_16x16x32_bf16 v[124:127], v[214:217], v[178:181], v[124:127]
	v_mfma_f32_16x16x32_bf16 v[68:71], v[218:221], v[178:181], v[68:71]
	ds_read_b128 v[178:181], v25
	s_mov_b32 m0, s47
	v_mfma_f32_16x16x32_bf16 v[136:139], v[214:217], v[222:225], v[136:139]
	global_load_lds_dwordx4 v4, s[68:69]
	v_mfma_f32_16x16x32_bf16 v[84:87], v[218:221], v[222:225], v[84:87]
	ds_read_b128 v[222:225], v26
	v_mfma_f32_16x16x32_bf16 v[150:153], v[214:217], v[226:229], v[150:153]
	ds_read_b128 v[214:217], v23
	v_mfma_f32_16x16x32_bf16 v[154:157], v[218:221], v[226:229], v[154:157]
	ds_read_b128 v[218:221], v22
	ds_read_b128 v[226:229], v27
	s_waitcnt lgkmcnt(6)
	v_mfma_f32_16x16x32_bf16 v[40:43], v[158:161], v[166:169], v[40:43]
	s_waitcnt lgkmcnt(5)
	s_mov_b32 m0, s49
	v_mfma_f32_16x16x32_bf16 v[44:47], v[162:165], v[166:169], v[44:47]
	global_load_lds_dwordx4 v146, s[64:65]
	s_waitcnt lgkmcnt(4)
	v_mfma_f32_16x16x32_bf16 v[56:59], v[158:161], v[178:181], v[56:59]
	v_mfma_f32_16x16x32_bf16 v[60:63], v[162:165], v[178:181], v[60:63]
	s_waitcnt lgkmcnt(3)
	v_mfma_f32_16x16x32_bf16 v[72:75], v[158:161], v[222:225], v[72:75]
	v_mfma_f32_16x16x32_bf16 v[76:79], v[162:165], v[222:225], v[76:79]
	s_waitcnt lgkmcnt(2)
	s_mov_b32 m0, s50
	v_mfma_f32_16x16x32_bf16 v[48:51], v[214:217], v[166:169], v[48:51]
	global_load_lds_dwordx4 v146, s[68:69]
	s_waitcnt lgkmcnt(1)
	v_mfma_f32_16x16x32_bf16 v[174:177], v[218:221], v[166:169], v[174:177]
	ds_read_b128 v[166:169], v28
	v_mfma_f32_16x16x32_bf16 v[64:67], v[214:217], v[178:181], v[64:67]
	v_mfma_f32_16x16x32_bf16 v[170:173], v[218:221], v[178:181], v[170:173]
	ds_read_b128 v[178:181], v29
	v_mfma_f32_16x16x32_bf16 v[80:83], v[214:217], v[222:225], v[80:83]
	v_mfma_f32_16x16x32_bf16 v[32:35], v[218:221], v[222:225], v[32:35]
	ds_read_b128 v[222:225], v30
	s_waitcnt lgkmcnt(3)
	v_mfma_f32_16x16x32_bf16 v[88:91], v[158:161], v[226:229], v[88:91]
	v_mfma_f32_16x16x32_bf16 v[92:95], v[162:165], v[226:229], v[92:95]
	v_mfma_f32_16x16x32_bf16 v[96:99], v[214:217], v[226:229], v[96:99]
	v_mfma_f32_16x16x32_bf16 v[36:39], v[218:221], v[226:229], v[36:39]
	ds_read_b128 v[226:229], v31
	s_waitcnt lgkmcnt(3)
	v_mfma_f32_16x16x32_bf16 v[104:107], v[158:161], v[166:169], v[104:107]
	v_mfma_f32_16x16x32_bf16 v[108:111], v[162:165], v[166:169], v[108:111]
	v_mfma_f32_16x16x32_bf16 v[112:115], v[214:217], v[166:169], v[112:115]
	v_mfma_f32_16x16x32_bf16 v[52:55], v[218:221], v[166:169], v[52:55]
	s_waitcnt lgkmcnt(2)
	v_mfma_f32_16x16x32_bf16 v[116:119], v[158:161], v[178:181], v[116:119]
	v_mfma_f32_16x16x32_bf16 v[120:123], v[162:165], v[178:181], v[120:123]
	v_mfma_f32_16x16x32_bf16 v[124:127], v[214:217], v[178:181], v[124:127]
	v_mfma_f32_16x16x32_bf16 v[68:71], v[218:221], v[178:181], v[68:71]
	s_waitcnt lgkmcnt(1)
	v_mfma_f32_16x16x32_bf16 v[128:131], v[158:161], v[222:225], v[128:131]
	v_mfma_f32_16x16x32_bf16 v[132:135], v[162:165], v[222:225], v[132:135]
	v_mfma_f32_16x16x32_bf16 v[136:139], v[214:217], v[222:225], v[136:139]
	v_mfma_f32_16x16x32_bf16 v[84:87], v[218:221], v[222:225], v[84:87]
	s_waitcnt lgkmcnt(0)
	v_mfma_f32_16x16x32_bf16 v[100:103], v[158:161], v[226:229], v[100:103]
	v_mfma_f32_16x16x32_bf16 v[140:143], v[162:165], v[226:229], v[140:143]
	v_mfma_f32_16x16x32_bf16 v[150:153], v[214:217], v[226:229], v[150:153]
	v_mfma_f32_16x16x32_bf16 v[154:157], v[218:221], v[226:229], v[154:157]
	s_add_u32 s64, s0, 0x2880
	s_addc_u32 s65, s1, 0
	s_add_u32 s68, s14, 0x2880
	s_waitcnt vmcnt(0)
	s_barrier
	s_addc_u32 s69, s15, 0
	ds_read_b128 v[158:161], v7 offset:32768
	ds_read_b128 v[162:165], v6
	ds_read_b128 v[166:169], v7 offset:34816
	ds_read_b128 v[178:181], v6 offset:2048
	ds_read_b128 v[214:217], v7 offset:36864
	ds_read_b128 v[218:221], v7 offset:38912
	ds_read_b128 v[222:225], v6 offset:4096
	ds_read_b128 v[226:229], v6 offset:6144
	s_waitcnt lgkmcnt(6)
	v_mfma_f32_16x16x32_bf16 v[40:43], v[158:161], v[162:165], v[40:43]
	s_waitcnt lgkmcnt(5)
	v_mfma_f32_16x16x32_bf16 v[44:47], v[166:169], v[162:165], v[44:47]
	s_waitcnt lgkmcnt(4)
	v_mfma_f32_16x16x32_bf16 v[56:59], v[158:161], v[178:181], v[56:59]
	s_mov_b32 m0, s52
	v_mfma_f32_16x16x32_bf16 v[60:63], v[166:169], v[178:181], v[60:63]
	global_load_lds_dwordx4 v0, s[64:65]
	s_waitcnt lgkmcnt(3)
	v_mfma_f32_16x16x32_bf16 v[48:51], v[214:217], v[162:165], v[48:51]
	v_mfma_f32_16x16x32_bf16 v[64:67], v[214:217], v[178:181], v[64:67]
	s_waitcnt lgkmcnt(2)
	v_mfma_f32_16x16x32_bf16 v[174:177], v[218:221], v[162:165], v[174:177]
	ds_read_b128 v[162:165], v6 offset:8192
	v_mfma_f32_16x16x32_bf16 v[170:173], v[218:221], v[178:181], v[170:173]
	ds_read_b128 v[178:181], v6 offset:10240
	s_waitcnt lgkmcnt(3)
	s_mov_b32 m0, s51
	v_mfma_f32_16x16x32_bf16 v[72:75], v[158:161], v[222:225], v[72:75]
	global_load_lds_dwordx4 v0, s[68:69]
	v_mfma_f32_16x16x32_bf16 v[76:79], v[166:169], v[222:225], v[76:79]
	v_mfma_f32_16x16x32_bf16 v[80:83], v[214:217], v[222:225], v[80:83]
	v_mfma_f32_16x16x32_bf16 v[32:35], v[218:221], v[222:225], v[32:35]
	ds_read_b128 v[222:225], v6 offset:12288
	s_waitcnt lgkmcnt(3)
	v_mfma_f32_16x16x32_bf16 v[88:91], v[158:161], v[226:229], v[88:91]
	s_mov_b32 m0, s53
	v_mfma_f32_16x16x32_bf16 v[92:95], v[166:169], v[226:229], v[92:95]
	global_load_lds_dwordx4 v2, s[64:65]
	v_mfma_f32_16x16x32_bf16 v[96:99], v[214:217], v[226:229], v[96:99]
	v_mfma_f32_16x16x32_bf16 v[36:39], v[218:221], v[226:229], v[36:39]
	ds_read_b128 v[226:229], v6 offset:14336
	s_waitcnt lgkmcnt(3)
	v_mfma_f32_16x16x32_bf16 v[104:107], v[158:161], v[162:165], v[104:107]
	s_waitcnt lgkmcnt(2)
	v_mfma_f32_16x16x32_bf16 v[116:119], v[158:161], v[178:181], v[116:119]
	s_waitcnt lgkmcnt(1)
	s_mov_b32 m0, s54
	v_mfma_f32_16x16x32_bf16 v[128:131], v[158:161], v[222:225], v[128:131]
	global_load_lds_dwordx4 v2, s[68:69]
	s_waitcnt lgkmcnt(0)
	v_mfma_f32_16x16x32_bf16 v[100:103], v[158:161], v[226:229], v[100:103]
	ds_read_b128 v[158:161], v7 offset:33792
	v_mfma_f32_16x16x32_bf16 v[108:111], v[166:169], v[162:165], v[108:111]
	v_mfma_f32_16x16x32_bf16 v[120:123], v[166:169], v[178:181], v[120:123]
	v_mfma_f32_16x16x32_bf16 v[132:135], v[166:169], v[222:225], v[132:135]
	s_mov_b32 m0, s55
	v_mfma_f32_16x16x32_bf16 v[140:143], v[166:169], v[226:229], v[140:143]
	global_load_lds_dwordx4 v4, s[64:65]
	ds_read_b128 v[166:169], v6 offset:1024
	v_mfma_f32_16x16x32_bf16 v[112:115], v[214:217], v[162:165], v[112:115]
	v_mfma_f32_16x16x32_bf16 v[52:55], v[218:221], v[162:165], v[52:55]
	ds_read_b128 v[162:165], v7 offset:35840
	v_mfma_f32_16x16x32_bf16 v[124:127], v[214:217], v[178:181], v[124:127]
	v_mfma_f32_16x16x32_bf16 v[68:71], v[218:221], v[178:181], v[68:71]
	ds_read_b128 v[178:181], v6 offset:3072
	s_mov_b32 m0, s58
	v_mfma_f32_16x16x32_bf16 v[136:139], v[214:217], v[222:225], v[136:139]
	global_load_lds_dwordx4 v4, s[68:69]
	v_mfma_f32_16x16x32_bf16 v[84:87], v[218:221], v[222:225], v[84:87]
	ds_read_b128 v[222:225], v6 offset:5120
	v_mfma_f32_16x16x32_bf16 v[150:153], v[214:217], v[226:229], v[150:153]
	ds_read_b128 v[214:217], v7 offset:37888
	v_mfma_f32_16x16x32_bf16 v[154:157], v[218:221], v[226:229], v[154:157]
	ds_read_b128 v[218:221], v7 offset:39936
	ds_read_b128 v[226:229], v6 offset:7168
	s_waitcnt lgkmcnt(6)
	v_mfma_f32_16x16x32_bf16 v[40:43], v[158:161], v[166:169], v[40:43]
	s_waitcnt lgkmcnt(5)
	s_mov_b32 m0, s62
	v_mfma_f32_16x16x32_bf16 v[44:47], v[162:165], v[166:169], v[44:47]
	global_load_lds_dwordx4 v146, s[64:65]
	s_waitcnt lgkmcnt(4)
	v_mfma_f32_16x16x32_bf16 v[56:59], v[158:161], v[178:181], v[56:59]
	v_mfma_f32_16x16x32_bf16 v[60:63], v[162:165], v[178:181], v[60:63]
	s_waitcnt lgkmcnt(3)
	v_mfma_f32_16x16x32_bf16 v[72:75], v[158:161], v[222:225], v[72:75]
	v_mfma_f32_16x16x32_bf16 v[76:79], v[162:165], v[222:225], v[76:79]
	s_waitcnt lgkmcnt(2)
	s_mov_b32 m0, s63
	v_mfma_f32_16x16x32_bf16 v[48:51], v[214:217], v[166:169], v[48:51]
	global_load_lds_dwordx4 v146, s[68:69]
	s_waitcnt lgkmcnt(1)
	v_mfma_f32_16x16x32_bf16 v[174:177], v[218:221], v[166:169], v[174:177]
	ds_read_b128 v[166:169], v6 offset:9216
	v_mfma_f32_16x16x32_bf16 v[64:67], v[214:217], v[178:181], v[64:67]
	v_mfma_f32_16x16x32_bf16 v[170:173], v[218:221], v[178:181], v[170:173]
	ds_read_b128 v[178:181], v6 offset:11264
	v_mfma_f32_16x16x32_bf16 v[80:83], v[214:217], v[222:225], v[80:83]
	v_mfma_f32_16x16x32_bf16 v[32:35], v[218:221], v[222:225], v[32:35]
	ds_read_b128 v[222:225], v6 offset:13312
	s_waitcnt lgkmcnt(3)
	v_mfma_f32_16x16x32_bf16 v[88:91], v[158:161], v[226:229], v[88:91]
	v_mfma_f32_16x16x32_bf16 v[92:95], v[162:165], v[226:229], v[92:95]
	v_mfma_f32_16x16x32_bf16 v[96:99], v[214:217], v[226:229], v[96:99]
	v_mfma_f32_16x16x32_bf16 v[36:39], v[218:221], v[226:229], v[36:39]
	ds_read_b128 v[226:229], v6 offset:15360
	s_waitcnt lgkmcnt(3)
	v_mfma_f32_16x16x32_bf16 v[104:107], v[158:161], v[166:169], v[104:107]
	v_mfma_f32_16x16x32_bf16 v[108:111], v[162:165], v[166:169], v[108:111]
	v_mfma_f32_16x16x32_bf16 v[112:115], v[214:217], v[166:169], v[112:115]
	v_mfma_f32_16x16x32_bf16 v[52:55], v[218:221], v[166:169], v[52:55]
	s_waitcnt lgkmcnt(2)
	v_mfma_f32_16x16x32_bf16 v[116:119], v[158:161], v[178:181], v[116:119]
	v_mfma_f32_16x16x32_bf16 v[120:123], v[162:165], v[178:181], v[120:123]
	v_mfma_f32_16x16x32_bf16 v[124:127], v[214:217], v[178:181], v[124:127]
	v_mfma_f32_16x16x32_bf16 v[68:71], v[218:221], v[178:181], v[68:71]
	s_waitcnt lgkmcnt(1)
	v_mfma_f32_16x16x32_bf16 v[128:131], v[158:161], v[222:225], v[128:131]
	v_mfma_f32_16x16x32_bf16 v[132:135], v[162:165], v[222:225], v[132:135]
	v_mfma_f32_16x16x32_bf16 v[136:139], v[214:217], v[222:225], v[136:139]
	v_mfma_f32_16x16x32_bf16 v[84:87], v[218:221], v[222:225], v[84:87]
	s_waitcnt lgkmcnt(0)
	v_mfma_f32_16x16x32_bf16 v[100:103], v[158:161], v[226:229], v[100:103]
	v_mfma_f32_16x16x32_bf16 v[140:143], v[162:165], v[226:229], v[140:143]
	v_mfma_f32_16x16x32_bf16 v[150:153], v[214:217], v[226:229], v[150:153]
	v_mfma_f32_16x16x32_bf16 v[154:157], v[218:221], v[226:229], v[154:157]
	s_add_u32 s64, s0, 0x2900
	s_addc_u32 s65, s1, 0
	s_add_u32 s68, s14, 0x2900
	s_waitcnt vmcnt(0)
	s_barrier
	s_addc_u32 s69, s15, 0
	ds_read_b128 v[158:161], v8
	ds_read_b128 v[162:165], v12
	ds_read_b128 v[166:169], v9
	ds_read_b128 v[178:181], v13
	ds_read_b128 v[214:217], v11
	ds_read_b128 v[218:221], v10
	ds_read_b128 v[222:225], v14
	ds_read_b128 v[226:229], v15
	s_waitcnt lgkmcnt(6)
	v_mfma_f32_16x16x32_bf16 v[40:43], v[158:161], v[162:165], v[40:43]
	s_waitcnt lgkmcnt(5)
	v_mfma_f32_16x16x32_bf16 v[44:47], v[166:169], v[162:165], v[44:47]
	s_waitcnt lgkmcnt(4)
	v_mfma_f32_16x16x32_bf16 v[56:59], v[158:161], v[178:181], v[56:59]
	s_mov_b32 m0, s42
	v_mfma_f32_16x16x32_bf16 v[60:63], v[166:169], v[178:181], v[60:63]
	global_load_lds_dwordx4 v0, s[64:65]
	s_waitcnt lgkmcnt(3)
	v_mfma_f32_16x16x32_bf16 v[48:51], v[214:217], v[162:165], v[48:51]
	v_mfma_f32_16x16x32_bf16 v[64:67], v[214:217], v[178:181], v[64:67]
	s_waitcnt lgkmcnt(2)
	v_mfma_f32_16x16x32_bf16 v[174:177], v[218:221], v[162:165], v[174:177]
	ds_read_b128 v[162:165], v16
	v_mfma_f32_16x16x32_bf16 v[170:173], v[218:221], v[178:181], v[170:173]
	ds_read_b128 v[178:181], v17
	s_waitcnt lgkmcnt(3)
	s_mov_b32 m0, s43
	v_mfma_f32_16x16x32_bf16 v[72:75], v[158:161], v[222:225], v[72:75]
	global_load_lds_dwordx4 v0, s[68:69]
	v_mfma_f32_16x16x32_bf16 v[76:79], v[166:169], v[222:225], v[76:79]
	v_mfma_f32_16x16x32_bf16 v[80:83], v[214:217], v[222:225], v[80:83]
	v_mfma_f32_16x16x32_bf16 v[32:35], v[218:221], v[222:225], v[32:35]
	ds_read_b128 v[222:225], v18
	s_waitcnt lgkmcnt(3)
	v_mfma_f32_16x16x32_bf16 v[88:91], v[158:161], v[226:229], v[88:91]
	s_mov_b32 m0, s44
	v_mfma_f32_16x16x32_bf16 v[92:95], v[166:169], v[226:229], v[92:95]
	global_load_lds_dwordx4 v2, s[64:65]
	v_mfma_f32_16x16x32_bf16 v[96:99], v[214:217], v[226:229], v[96:99]
	v_mfma_f32_16x16x32_bf16 v[36:39], v[218:221], v[226:229], v[36:39]
	ds_read_b128 v[226:229], v19
	s_waitcnt lgkmcnt(3)
	v_mfma_f32_16x16x32_bf16 v[104:107], v[158:161], v[162:165], v[104:107]
	s_waitcnt lgkmcnt(2)
	v_mfma_f32_16x16x32_bf16 v[116:119], v[158:161], v[178:181], v[116:119]
	s_waitcnt lgkmcnt(1)
	s_mov_b32 m0, s45
	v_mfma_f32_16x16x32_bf16 v[128:131], v[158:161], v[222:225], v[128:131]
	global_load_lds_dwordx4 v2, s[68:69]
	s_waitcnt lgkmcnt(0)
	v_mfma_f32_16x16x32_bf16 v[100:103], v[158:161], v[226:229], v[100:103]
	ds_read_b128 v[158:161], v20
	v_mfma_f32_16x16x32_bf16 v[108:111], v[166:169], v[162:165], v[108:111]
	v_mfma_f32_16x16x32_bf16 v[120:123], v[166:169], v[178:181], v[120:123]
	v_mfma_f32_16x16x32_bf16 v[132:135], v[166:169], v[222:225], v[132:135]
	s_mov_b32 m0, s46
	v_mfma_f32_16x16x32_bf16 v[140:143], v[166:169], v[226:229], v[140:143]
	global_load_lds_dwordx4 v4, s[64:65]
	ds_read_b128 v[166:169], v24
	v_mfma_f32_16x16x32_bf16 v[112:115], v[214:217], v[162:165], v[112:115]
	v_mfma_f32_16x16x32_bf16 v[52:55], v[218:221], v[162:165], v[52:55]
	ds_read_b128 v[162:165], v21
	v_mfma_f32_16x16x32_bf16 v[124:127], v[214:217], v[178:181], v[124:127]
	v_mfma_f32_16x16x32_bf16 v[68:71], v[218:221], v[178:181], v[68:71]
	ds_read_b128 v[178:181], v25
	s_mov_b32 m0, s47
	v_mfma_f32_16x16x32_bf16 v[136:139], v[214:217], v[222:225], v[136:139]
	global_load_lds_dwordx4 v4, s[68:69]
	v_mfma_f32_16x16x32_bf16 v[84:87], v[218:221], v[222:225], v[84:87]
	ds_read_b128 v[222:225], v26
	v_mfma_f32_16x16x32_bf16 v[150:153], v[214:217], v[226:229], v[150:153]
	ds_read_b128 v[214:217], v23
	v_mfma_f32_16x16x32_bf16 v[154:157], v[218:221], v[226:229], v[154:157]
	ds_read_b128 v[218:221], v22
	ds_read_b128 v[226:229], v27
	s_waitcnt lgkmcnt(6)
	v_mfma_f32_16x16x32_bf16 v[40:43], v[158:161], v[166:169], v[40:43]
	s_waitcnt lgkmcnt(5)
	s_mov_b32 m0, s49
	v_mfma_f32_16x16x32_bf16 v[44:47], v[162:165], v[166:169], v[44:47]
	global_load_lds_dwordx4 v146, s[64:65]
	s_waitcnt lgkmcnt(4)
	v_mfma_f32_16x16x32_bf16 v[56:59], v[158:161], v[178:181], v[56:59]
	v_mfma_f32_16x16x32_bf16 v[60:63], v[162:165], v[178:181], v[60:63]
	s_waitcnt lgkmcnt(3)
	v_mfma_f32_16x16x32_bf16 v[72:75], v[158:161], v[222:225], v[72:75]
	v_mfma_f32_16x16x32_bf16 v[76:79], v[162:165], v[222:225], v[76:79]
	s_waitcnt lgkmcnt(2)
	s_mov_b32 m0, s50
	v_mfma_f32_16x16x32_bf16 v[48:51], v[214:217], v[166:169], v[48:51]
	global_load_lds_dwordx4 v146, s[68:69]
	s_waitcnt lgkmcnt(1)
	v_mfma_f32_16x16x32_bf16 v[174:177], v[218:221], v[166:169], v[174:177]
	ds_read_b128 v[166:169], v28
	v_mfma_f32_16x16x32_bf16 v[64:67], v[214:217], v[178:181], v[64:67]
	v_mfma_f32_16x16x32_bf16 v[170:173], v[218:221], v[178:181], v[170:173]
	ds_read_b128 v[178:181], v29
	v_mfma_f32_16x16x32_bf16 v[80:83], v[214:217], v[222:225], v[80:83]
	v_mfma_f32_16x16x32_bf16 v[32:35], v[218:221], v[222:225], v[32:35]
	ds_read_b128 v[222:225], v30
	s_waitcnt lgkmcnt(3)
	v_mfma_f32_16x16x32_bf16 v[88:91], v[158:161], v[226:229], v[88:91]
	v_mfma_f32_16x16x32_bf16 v[92:95], v[162:165], v[226:229], v[92:95]
	v_mfma_f32_16x16x32_bf16 v[96:99], v[214:217], v[226:229], v[96:99]
	v_mfma_f32_16x16x32_bf16 v[36:39], v[218:221], v[226:229], v[36:39]
	ds_read_b128 v[226:229], v31
	s_waitcnt lgkmcnt(3)
	v_mfma_f32_16x16x32_bf16 v[104:107], v[158:161], v[166:169], v[104:107]
	v_mfma_f32_16x16x32_bf16 v[108:111], v[162:165], v[166:169], v[108:111]
	v_mfma_f32_16x16x32_bf16 v[112:115], v[214:217], v[166:169], v[112:115]
	v_mfma_f32_16x16x32_bf16 v[52:55], v[218:221], v[166:169], v[52:55]
	s_waitcnt lgkmcnt(2)
	v_mfma_f32_16x16x32_bf16 v[116:119], v[158:161], v[178:181], v[116:119]
	v_mfma_f32_16x16x32_bf16 v[120:123], v[162:165], v[178:181], v[120:123]
	v_mfma_f32_16x16x32_bf16 v[124:127], v[214:217], v[178:181], v[124:127]
	v_mfma_f32_16x16x32_bf16 v[68:71], v[218:221], v[178:181], v[68:71]
	s_waitcnt lgkmcnt(1)
	v_mfma_f32_16x16x32_bf16 v[128:131], v[158:161], v[222:225], v[128:131]
	v_mfma_f32_16x16x32_bf16 v[132:135], v[162:165], v[222:225], v[132:135]
	v_mfma_f32_16x16x32_bf16 v[136:139], v[214:217], v[222:225], v[136:139]
	v_mfma_f32_16x16x32_bf16 v[84:87], v[218:221], v[222:225], v[84:87]
	s_waitcnt lgkmcnt(0)
	v_mfma_f32_16x16x32_bf16 v[100:103], v[158:161], v[226:229], v[100:103]
	v_mfma_f32_16x16x32_bf16 v[140:143], v[162:165], v[226:229], v[140:143]
	v_mfma_f32_16x16x32_bf16 v[150:153], v[214:217], v[226:229], v[150:153]
	v_mfma_f32_16x16x32_bf16 v[154:157], v[218:221], v[226:229], v[154:157]
	s_add_u32 s64, s0, 0x2980
	s_addc_u32 s65, s1, 0
	s_add_u32 s68, s14, 0x2980
	s_waitcnt vmcnt(0)
	s_barrier
	s_addc_u32 s69, s15, 0
	ds_read_b128 v[158:161], v7 offset:32768
	ds_read_b128 v[162:165], v6
	ds_read_b128 v[166:169], v7 offset:34816
	ds_read_b128 v[178:181], v6 offset:2048
	ds_read_b128 v[214:217], v7 offset:36864
	ds_read_b128 v[218:221], v7 offset:38912
	ds_read_b128 v[222:225], v6 offset:4096
	ds_read_b128 v[226:229], v6 offset:6144
	s_waitcnt lgkmcnt(6)
	v_mfma_f32_16x16x32_bf16 v[40:43], v[158:161], v[162:165], v[40:43]
	s_waitcnt lgkmcnt(5)
	v_mfma_f32_16x16x32_bf16 v[44:47], v[166:169], v[162:165], v[44:47]
	s_waitcnt lgkmcnt(4)
	v_mfma_f32_16x16x32_bf16 v[56:59], v[158:161], v[178:181], v[56:59]
	s_mov_b32 m0, s52
	v_mfma_f32_16x16x32_bf16 v[60:63], v[166:169], v[178:181], v[60:63]
	global_load_lds_dwordx4 v0, s[64:65]
	s_waitcnt lgkmcnt(3)
	v_mfma_f32_16x16x32_bf16 v[48:51], v[214:217], v[162:165], v[48:51]
	v_mfma_f32_16x16x32_bf16 v[64:67], v[214:217], v[178:181], v[64:67]
	s_waitcnt lgkmcnt(2)
	v_mfma_f32_16x16x32_bf16 v[174:177], v[218:221], v[162:165], v[174:177]
	ds_read_b128 v[162:165], v6 offset:8192
	v_mfma_f32_16x16x32_bf16 v[170:173], v[218:221], v[178:181], v[170:173]
	ds_read_b128 v[178:181], v6 offset:10240
	s_waitcnt lgkmcnt(3)
	s_mov_b32 m0, s51
	v_mfma_f32_16x16x32_bf16 v[72:75], v[158:161], v[222:225], v[72:75]
	global_load_lds_dwordx4 v0, s[68:69]
	v_mfma_f32_16x16x32_bf16 v[76:79], v[166:169], v[222:225], v[76:79]
	v_mfma_f32_16x16x32_bf16 v[80:83], v[214:217], v[222:225], v[80:83]
	v_mfma_f32_16x16x32_bf16 v[32:35], v[218:221], v[222:225], v[32:35]
	ds_read_b128 v[222:225], v6 offset:12288
	s_waitcnt lgkmcnt(3)
	v_mfma_f32_16x16x32_bf16 v[88:91], v[158:161], v[226:229], v[88:91]
	s_mov_b32 m0, s53
	v_mfma_f32_16x16x32_bf16 v[92:95], v[166:169], v[226:229], v[92:95]
	global_load_lds_dwordx4 v2, s[64:65]
	v_mfma_f32_16x16x32_bf16 v[96:99], v[214:217], v[226:229], v[96:99]
	v_mfma_f32_16x16x32_bf16 v[36:39], v[218:221], v[226:229], v[36:39]
	ds_read_b128 v[226:229], v6 offset:14336
	s_waitcnt lgkmcnt(3)
	v_mfma_f32_16x16x32_bf16 v[104:107], v[158:161], v[162:165], v[104:107]
	s_waitcnt lgkmcnt(2)
	v_mfma_f32_16x16x32_bf16 v[116:119], v[158:161], v[178:181], v[116:119]
	s_waitcnt lgkmcnt(1)
	s_mov_b32 m0, s54
	v_mfma_f32_16x16x32_bf16 v[128:131], v[158:161], v[222:225], v[128:131]
	global_load_lds_dwordx4 v2, s[68:69]
	s_waitcnt lgkmcnt(0)
	v_mfma_f32_16x16x32_bf16 v[100:103], v[158:161], v[226:229], v[100:103]
	ds_read_b128 v[158:161], v7 offset:33792
	v_mfma_f32_16x16x32_bf16 v[108:111], v[166:169], v[162:165], v[108:111]
	v_mfma_f32_16x16x32_bf16 v[120:123], v[166:169], v[178:181], v[120:123]
	v_mfma_f32_16x16x32_bf16 v[132:135], v[166:169], v[222:225], v[132:135]
	s_mov_b32 m0, s55
	v_mfma_f32_16x16x32_bf16 v[140:143], v[166:169], v[226:229], v[140:143]
	global_load_lds_dwordx4 v4, s[64:65]
	ds_read_b128 v[166:169], v6 offset:1024
	v_mfma_f32_16x16x32_bf16 v[112:115], v[214:217], v[162:165], v[112:115]
	v_mfma_f32_16x16x32_bf16 v[52:55], v[218:221], v[162:165], v[52:55]
	ds_read_b128 v[162:165], v7 offset:35840
	v_mfma_f32_16x16x32_bf16 v[124:127], v[214:217], v[178:181], v[124:127]
	v_mfma_f32_16x16x32_bf16 v[68:71], v[218:221], v[178:181], v[68:71]
	ds_read_b128 v[178:181], v6 offset:3072
	s_mov_b32 m0, s58
	v_mfma_f32_16x16x32_bf16 v[136:139], v[214:217], v[222:225], v[136:139]
	global_load_lds_dwordx4 v4, s[68:69]
	v_mfma_f32_16x16x32_bf16 v[84:87], v[218:221], v[222:225], v[84:87]
	ds_read_b128 v[222:225], v6 offset:5120
	v_mfma_f32_16x16x32_bf16 v[150:153], v[214:217], v[226:229], v[150:153]
	ds_read_b128 v[214:217], v7 offset:37888
	v_mfma_f32_16x16x32_bf16 v[154:157], v[218:221], v[226:229], v[154:157]
	ds_read_b128 v[218:221], v7 offset:39936
	ds_read_b128 v[226:229], v6 offset:7168
	s_waitcnt lgkmcnt(6)
	v_mfma_f32_16x16x32_bf16 v[40:43], v[158:161], v[166:169], v[40:43]
	s_waitcnt lgkmcnt(5)
	s_mov_b32 m0, s62
	v_mfma_f32_16x16x32_bf16 v[44:47], v[162:165], v[166:169], v[44:47]
	global_load_lds_dwordx4 v146, s[64:65]
	s_waitcnt lgkmcnt(4)
	v_mfma_f32_16x16x32_bf16 v[56:59], v[158:161], v[178:181], v[56:59]
	v_mfma_f32_16x16x32_bf16 v[60:63], v[162:165], v[178:181], v[60:63]
	s_waitcnt lgkmcnt(3)
	v_mfma_f32_16x16x32_bf16 v[72:75], v[158:161], v[222:225], v[72:75]
	v_mfma_f32_16x16x32_bf16 v[76:79], v[162:165], v[222:225], v[76:79]
	s_waitcnt lgkmcnt(2)
	s_mov_b32 m0, s63
	v_mfma_f32_16x16x32_bf16 v[48:51], v[214:217], v[166:169], v[48:51]
	global_load_lds_dwordx4 v146, s[68:69]
	s_waitcnt lgkmcnt(1)
	v_mfma_f32_16x16x32_bf16 v[174:177], v[218:221], v[166:169], v[174:177]
	ds_read_b128 v[166:169], v6 offset:9216
	v_mfma_f32_16x16x32_bf16 v[64:67], v[214:217], v[178:181], v[64:67]
	v_mfma_f32_16x16x32_bf16 v[170:173], v[218:221], v[178:181], v[170:173]
	ds_read_b128 v[178:181], v6 offset:11264
	v_mfma_f32_16x16x32_bf16 v[80:83], v[214:217], v[222:225], v[80:83]
	v_mfma_f32_16x16x32_bf16 v[32:35], v[218:221], v[222:225], v[32:35]
	ds_read_b128 v[222:225], v6 offset:13312
	s_waitcnt lgkmcnt(3)
	v_mfma_f32_16x16x32_bf16 v[88:91], v[158:161], v[226:229], v[88:91]
	v_mfma_f32_16x16x32_bf16 v[92:95], v[162:165], v[226:229], v[92:95]
	v_mfma_f32_16x16x32_bf16 v[96:99], v[214:217], v[226:229], v[96:99]
	v_mfma_f32_16x16x32_bf16 v[36:39], v[218:221], v[226:229], v[36:39]
	ds_read_b128 v[226:229], v6 offset:15360
	s_waitcnt lgkmcnt(3)
	v_mfma_f32_16x16x32_bf16 v[104:107], v[158:161], v[166:169], v[104:107]
	v_mfma_f32_16x16x32_bf16 v[108:111], v[162:165], v[166:169], v[108:111]
	v_mfma_f32_16x16x32_bf16 v[112:115], v[214:217], v[166:169], v[112:115]
	v_mfma_f32_16x16x32_bf16 v[52:55], v[218:221], v[166:169], v[52:55]
	s_waitcnt lgkmcnt(2)
	v_mfma_f32_16x16x32_bf16 v[116:119], v[158:161], v[178:181], v[116:119]
	v_mfma_f32_16x16x32_bf16 v[120:123], v[162:165], v[178:181], v[120:123]
	v_mfma_f32_16x16x32_bf16 v[124:127], v[214:217], v[178:181], v[124:127]
	v_mfma_f32_16x16x32_bf16 v[68:71], v[218:221], v[178:181], v[68:71]
	s_waitcnt lgkmcnt(1)
	v_mfma_f32_16x16x32_bf16 v[128:131], v[158:161], v[222:225], v[128:131]
	v_mfma_f32_16x16x32_bf16 v[132:135], v[162:165], v[222:225], v[132:135]
	v_mfma_f32_16x16x32_bf16 v[136:139], v[214:217], v[222:225], v[136:139]
	v_mfma_f32_16x16x32_bf16 v[84:87], v[218:221], v[222:225], v[84:87]
	s_waitcnt lgkmcnt(0)
	v_mfma_f32_16x16x32_bf16 v[100:103], v[158:161], v[226:229], v[100:103]
	v_mfma_f32_16x16x32_bf16 v[140:143], v[162:165], v[226:229], v[140:143]
	v_mfma_f32_16x16x32_bf16 v[150:153], v[214:217], v[226:229], v[150:153]
	v_mfma_f32_16x16x32_bf16 v[154:157], v[218:221], v[226:229], v[154:157]
	s_add_u32 s64, s0, 0x2a00
	s_addc_u32 s65, s1, 0
	s_add_u32 s68, s14, 0x2a00
	s_waitcnt vmcnt(0)
	s_barrier
	s_addc_u32 s69, s15, 0
	ds_read_b128 v[158:161], v8
	ds_read_b128 v[162:165], v12
	ds_read_b128 v[166:169], v9
	ds_read_b128 v[178:181], v13
	ds_read_b128 v[214:217], v11
	ds_read_b128 v[218:221], v10
	ds_read_b128 v[222:225], v14
	ds_read_b128 v[226:229], v15
	s_waitcnt lgkmcnt(6)
	v_mfma_f32_16x16x32_bf16 v[40:43], v[158:161], v[162:165], v[40:43]
	s_waitcnt lgkmcnt(5)
	v_mfma_f32_16x16x32_bf16 v[44:47], v[166:169], v[162:165], v[44:47]
	s_waitcnt lgkmcnt(4)
	v_mfma_f32_16x16x32_bf16 v[56:59], v[158:161], v[178:181], v[56:59]
	s_mov_b32 m0, s42
	v_mfma_f32_16x16x32_bf16 v[60:63], v[166:169], v[178:181], v[60:63]
	global_load_lds_dwordx4 v0, s[64:65]
	s_waitcnt lgkmcnt(3)
	v_mfma_f32_16x16x32_bf16 v[48:51], v[214:217], v[162:165], v[48:51]
	v_mfma_f32_16x16x32_bf16 v[64:67], v[214:217], v[178:181], v[64:67]
	s_waitcnt lgkmcnt(2)
	v_mfma_f32_16x16x32_bf16 v[174:177], v[218:221], v[162:165], v[174:177]
	ds_read_b128 v[162:165], v16
	v_mfma_f32_16x16x32_bf16 v[170:173], v[218:221], v[178:181], v[170:173]
	ds_read_b128 v[178:181], v17
	s_waitcnt lgkmcnt(3)
	s_mov_b32 m0, s43
	v_mfma_f32_16x16x32_bf16 v[72:75], v[158:161], v[222:225], v[72:75]
	global_load_lds_dwordx4 v0, s[68:69]
	v_mfma_f32_16x16x32_bf16 v[76:79], v[166:169], v[222:225], v[76:79]
	v_mfma_f32_16x16x32_bf16 v[80:83], v[214:217], v[222:225], v[80:83]
	v_mfma_f32_16x16x32_bf16 v[32:35], v[218:221], v[222:225], v[32:35]
	ds_read_b128 v[222:225], v18
	s_waitcnt lgkmcnt(3)
	v_mfma_f32_16x16x32_bf16 v[88:91], v[158:161], v[226:229], v[88:91]
	s_mov_b32 m0, s44
	v_mfma_f32_16x16x32_bf16 v[92:95], v[166:169], v[226:229], v[92:95]
	global_load_lds_dwordx4 v2, s[64:65]
	v_mfma_f32_16x16x32_bf16 v[96:99], v[214:217], v[226:229], v[96:99]
	v_mfma_f32_16x16x32_bf16 v[36:39], v[218:221], v[226:229], v[36:39]
	ds_read_b128 v[226:229], v19
	s_waitcnt lgkmcnt(3)
	v_mfma_f32_16x16x32_bf16 v[104:107], v[158:161], v[162:165], v[104:107]
	s_waitcnt lgkmcnt(2)
	v_mfma_f32_16x16x32_bf16 v[116:119], v[158:161], v[178:181], v[116:119]
	s_waitcnt lgkmcnt(1)
	s_mov_b32 m0, s45
	v_mfma_f32_16x16x32_bf16 v[128:131], v[158:161], v[222:225], v[128:131]
	global_load_lds_dwordx4 v2, s[68:69]
	s_waitcnt lgkmcnt(0)
	v_mfma_f32_16x16x32_bf16 v[100:103], v[158:161], v[226:229], v[100:103]
	ds_read_b128 v[158:161], v20
	v_mfma_f32_16x16x32_bf16 v[108:111], v[166:169], v[162:165], v[108:111]
	v_mfma_f32_16x16x32_bf16 v[120:123], v[166:169], v[178:181], v[120:123]
	v_mfma_f32_16x16x32_bf16 v[132:135], v[166:169], v[222:225], v[132:135]
	s_mov_b32 m0, s46
	v_mfma_f32_16x16x32_bf16 v[140:143], v[166:169], v[226:229], v[140:143]
	global_load_lds_dwordx4 v4, s[64:65]
	ds_read_b128 v[166:169], v24
	v_mfma_f32_16x16x32_bf16 v[112:115], v[214:217], v[162:165], v[112:115]
	v_mfma_f32_16x16x32_bf16 v[52:55], v[218:221], v[162:165], v[52:55]
	ds_read_b128 v[162:165], v21
	v_mfma_f32_16x16x32_bf16 v[124:127], v[214:217], v[178:181], v[124:127]
	v_mfma_f32_16x16x32_bf16 v[68:71], v[218:221], v[178:181], v[68:71]
	ds_read_b128 v[178:181], v25
	s_mov_b32 m0, s47
	v_mfma_f32_16x16x32_bf16 v[136:139], v[214:217], v[222:225], v[136:139]
	global_load_lds_dwordx4 v4, s[68:69]
	v_mfma_f32_16x16x32_bf16 v[84:87], v[218:221], v[222:225], v[84:87]
	ds_read_b128 v[222:225], v26
	v_mfma_f32_16x16x32_bf16 v[150:153], v[214:217], v[226:229], v[150:153]
	ds_read_b128 v[214:217], v23
	v_mfma_f32_16x16x32_bf16 v[154:157], v[218:221], v[226:229], v[154:157]
	ds_read_b128 v[218:221], v22
	ds_read_b128 v[226:229], v27
	s_waitcnt lgkmcnt(6)
	v_mfma_f32_16x16x32_bf16 v[40:43], v[158:161], v[166:169], v[40:43]
	s_waitcnt lgkmcnt(5)
	s_mov_b32 m0, s49
	v_mfma_f32_16x16x32_bf16 v[44:47], v[162:165], v[166:169], v[44:47]
	global_load_lds_dwordx4 v146, s[64:65]
	s_waitcnt lgkmcnt(4)
	v_mfma_f32_16x16x32_bf16 v[56:59], v[158:161], v[178:181], v[56:59]
	v_mfma_f32_16x16x32_bf16 v[60:63], v[162:165], v[178:181], v[60:63]
	s_waitcnt lgkmcnt(3)
	v_mfma_f32_16x16x32_bf16 v[72:75], v[158:161], v[222:225], v[72:75]
	v_mfma_f32_16x16x32_bf16 v[76:79], v[162:165], v[222:225], v[76:79]
	s_waitcnt lgkmcnt(2)
	s_mov_b32 m0, s50
	v_mfma_f32_16x16x32_bf16 v[48:51], v[214:217], v[166:169], v[48:51]
	global_load_lds_dwordx4 v146, s[68:69]
	s_waitcnt lgkmcnt(1)
	v_mfma_f32_16x16x32_bf16 v[174:177], v[218:221], v[166:169], v[174:177]
	ds_read_b128 v[166:169], v28
	v_mfma_f32_16x16x32_bf16 v[64:67], v[214:217], v[178:181], v[64:67]
	v_mfma_f32_16x16x32_bf16 v[170:173], v[218:221], v[178:181], v[170:173]
	ds_read_b128 v[178:181], v29
	v_mfma_f32_16x16x32_bf16 v[80:83], v[214:217], v[222:225], v[80:83]
	v_mfma_f32_16x16x32_bf16 v[32:35], v[218:221], v[222:225], v[32:35]
	ds_read_b128 v[222:225], v30
	s_waitcnt lgkmcnt(3)
	v_mfma_f32_16x16x32_bf16 v[88:91], v[158:161], v[226:229], v[88:91]
	v_mfma_f32_16x16x32_bf16 v[92:95], v[162:165], v[226:229], v[92:95]
	v_mfma_f32_16x16x32_bf16 v[96:99], v[214:217], v[226:229], v[96:99]
	v_mfma_f32_16x16x32_bf16 v[36:39], v[218:221], v[226:229], v[36:39]
	ds_read_b128 v[226:229], v31
	s_waitcnt lgkmcnt(3)
	v_mfma_f32_16x16x32_bf16 v[104:107], v[158:161], v[166:169], v[104:107]
	v_mfma_f32_16x16x32_bf16 v[108:111], v[162:165], v[166:169], v[108:111]
	v_mfma_f32_16x16x32_bf16 v[112:115], v[214:217], v[166:169], v[112:115]
	v_mfma_f32_16x16x32_bf16 v[52:55], v[218:221], v[166:169], v[52:55]
	s_waitcnt lgkmcnt(2)
	v_mfma_f32_16x16x32_bf16 v[116:119], v[158:161], v[178:181], v[116:119]
	v_mfma_f32_16x16x32_bf16 v[120:123], v[162:165], v[178:181], v[120:123]
	v_mfma_f32_16x16x32_bf16 v[124:127], v[214:217], v[178:181], v[124:127]
	v_mfma_f32_16x16x32_bf16 v[68:71], v[218:221], v[178:181], v[68:71]
	s_waitcnt lgkmcnt(1)
	v_mfma_f32_16x16x32_bf16 v[128:131], v[158:161], v[222:225], v[128:131]
	v_mfma_f32_16x16x32_bf16 v[132:135], v[162:165], v[222:225], v[132:135]
	v_mfma_f32_16x16x32_bf16 v[136:139], v[214:217], v[222:225], v[136:139]
	v_mfma_f32_16x16x32_bf16 v[84:87], v[218:221], v[222:225], v[84:87]
	s_waitcnt lgkmcnt(0)
	v_mfma_f32_16x16x32_bf16 v[100:103], v[158:161], v[226:229], v[100:103]
	v_mfma_f32_16x16x32_bf16 v[140:143], v[162:165], v[226:229], v[140:143]
	v_mfma_f32_16x16x32_bf16 v[150:153], v[214:217], v[226:229], v[150:153]
	v_mfma_f32_16x16x32_bf16 v[154:157], v[218:221], v[226:229], v[154:157]
	s_add_u32 s64, s0, 0x2a80
	s_addc_u32 s65, s1, 0
	s_add_u32 s68, s14, 0x2a80
	s_waitcnt vmcnt(0)
	s_barrier
	s_addc_u32 s69, s15, 0
	ds_read_b128 v[158:161], v7 offset:32768
	ds_read_b128 v[162:165], v6
	ds_read_b128 v[166:169], v7 offset:34816
	ds_read_b128 v[178:181], v6 offset:2048
	ds_read_b128 v[214:217], v7 offset:36864
	ds_read_b128 v[218:221], v7 offset:38912
	ds_read_b128 v[222:225], v6 offset:4096
	ds_read_b128 v[226:229], v6 offset:6144
	s_waitcnt lgkmcnt(6)
	v_mfma_f32_16x16x32_bf16 v[40:43], v[158:161], v[162:165], v[40:43]
	s_waitcnt lgkmcnt(5)
	v_mfma_f32_16x16x32_bf16 v[44:47], v[166:169], v[162:165], v[44:47]
	s_waitcnt lgkmcnt(4)
	v_mfma_f32_16x16x32_bf16 v[56:59], v[158:161], v[178:181], v[56:59]
	s_mov_b32 m0, s52
	v_mfma_f32_16x16x32_bf16 v[60:63], v[166:169], v[178:181], v[60:63]
	global_load_lds_dwordx4 v0, s[64:65]
	s_waitcnt lgkmcnt(3)
	v_mfma_f32_16x16x32_bf16 v[48:51], v[214:217], v[162:165], v[48:51]
	v_mfma_f32_16x16x32_bf16 v[64:67], v[214:217], v[178:181], v[64:67]
	s_waitcnt lgkmcnt(2)
	v_mfma_f32_16x16x32_bf16 v[174:177], v[218:221], v[162:165], v[174:177]
	ds_read_b128 v[162:165], v6 offset:8192
	v_mfma_f32_16x16x32_bf16 v[170:173], v[218:221], v[178:181], v[170:173]
	ds_read_b128 v[178:181], v6 offset:10240
	s_waitcnt lgkmcnt(3)
	s_mov_b32 m0, s51
	v_mfma_f32_16x16x32_bf16 v[72:75], v[158:161], v[222:225], v[72:75]
	global_load_lds_dwordx4 v0, s[68:69]
	v_mfma_f32_16x16x32_bf16 v[76:79], v[166:169], v[222:225], v[76:79]
	v_mfma_f32_16x16x32_bf16 v[80:83], v[214:217], v[222:225], v[80:83]
	v_mfma_f32_16x16x32_bf16 v[32:35], v[218:221], v[222:225], v[32:35]
	ds_read_b128 v[222:225], v6 offset:12288
	s_waitcnt lgkmcnt(3)
	v_mfma_f32_16x16x32_bf16 v[88:91], v[158:161], v[226:229], v[88:91]
	s_mov_b32 m0, s53
	v_mfma_f32_16x16x32_bf16 v[92:95], v[166:169], v[226:229], v[92:95]
	global_load_lds_dwordx4 v2, s[64:65]
	v_mfma_f32_16x16x32_bf16 v[96:99], v[214:217], v[226:229], v[96:99]
	v_mfma_f32_16x16x32_bf16 v[36:39], v[218:221], v[226:229], v[36:39]
	ds_read_b128 v[226:229], v6 offset:14336
	s_waitcnt lgkmcnt(3)
	v_mfma_f32_16x16x32_bf16 v[104:107], v[158:161], v[162:165], v[104:107]
	s_waitcnt lgkmcnt(2)
	v_mfma_f32_16x16x32_bf16 v[116:119], v[158:161], v[178:181], v[116:119]
	s_waitcnt lgkmcnt(1)
	s_mov_b32 m0, s54
	v_mfma_f32_16x16x32_bf16 v[128:131], v[158:161], v[222:225], v[128:131]
	global_load_lds_dwordx4 v2, s[68:69]
	s_waitcnt lgkmcnt(0)
	v_mfma_f32_16x16x32_bf16 v[100:103], v[158:161], v[226:229], v[100:103]
	ds_read_b128 v[158:161], v7 offset:33792
	v_mfma_f32_16x16x32_bf16 v[108:111], v[166:169], v[162:165], v[108:111]
	v_mfma_f32_16x16x32_bf16 v[120:123], v[166:169], v[178:181], v[120:123]
	v_mfma_f32_16x16x32_bf16 v[132:135], v[166:169], v[222:225], v[132:135]
	s_mov_b32 m0, s55
	v_mfma_f32_16x16x32_bf16 v[140:143], v[166:169], v[226:229], v[140:143]
	global_load_lds_dwordx4 v4, s[64:65]
	ds_read_b128 v[166:169], v6 offset:1024
	v_mfma_f32_16x16x32_bf16 v[112:115], v[214:217], v[162:165], v[112:115]
	v_mfma_f32_16x16x32_bf16 v[52:55], v[218:221], v[162:165], v[52:55]
	ds_read_b128 v[162:165], v7 offset:35840
	v_mfma_f32_16x16x32_bf16 v[124:127], v[214:217], v[178:181], v[124:127]
	v_mfma_f32_16x16x32_bf16 v[68:71], v[218:221], v[178:181], v[68:71]
	ds_read_b128 v[178:181], v6 offset:3072
	s_mov_b32 m0, s58
	v_mfma_f32_16x16x32_bf16 v[136:139], v[214:217], v[222:225], v[136:139]
	global_load_lds_dwordx4 v4, s[68:69]
	v_mfma_f32_16x16x32_bf16 v[84:87], v[218:221], v[222:225], v[84:87]
	ds_read_b128 v[222:225], v6 offset:5120
	v_mfma_f32_16x16x32_bf16 v[150:153], v[214:217], v[226:229], v[150:153]
	ds_read_b128 v[214:217], v7 offset:37888
	v_mfma_f32_16x16x32_bf16 v[154:157], v[218:221], v[226:229], v[154:157]
	ds_read_b128 v[218:221], v7 offset:39936
	ds_read_b128 v[226:229], v6 offset:7168
	s_waitcnt lgkmcnt(6)
	v_mfma_f32_16x16x32_bf16 v[40:43], v[158:161], v[166:169], v[40:43]
	s_waitcnt lgkmcnt(5)
	s_mov_b32 m0, s62
	v_mfma_f32_16x16x32_bf16 v[44:47], v[162:165], v[166:169], v[44:47]
	global_load_lds_dwordx4 v146, s[64:65]
	s_waitcnt lgkmcnt(4)
	v_mfma_f32_16x16x32_bf16 v[56:59], v[158:161], v[178:181], v[56:59]
	v_mfma_f32_16x16x32_bf16 v[60:63], v[162:165], v[178:181], v[60:63]
	s_waitcnt lgkmcnt(3)
	v_mfma_f32_16x16x32_bf16 v[72:75], v[158:161], v[222:225], v[72:75]
	v_mfma_f32_16x16x32_bf16 v[76:79], v[162:165], v[222:225], v[76:79]
	s_waitcnt lgkmcnt(2)
	s_mov_b32 m0, s63
	v_mfma_f32_16x16x32_bf16 v[48:51], v[214:217], v[166:169], v[48:51]
	global_load_lds_dwordx4 v146, s[68:69]
	s_waitcnt lgkmcnt(1)
	v_mfma_f32_16x16x32_bf16 v[174:177], v[218:221], v[166:169], v[174:177]
	ds_read_b128 v[166:169], v6 offset:9216
	v_mfma_f32_16x16x32_bf16 v[64:67], v[214:217], v[178:181], v[64:67]
	v_mfma_f32_16x16x32_bf16 v[170:173], v[218:221], v[178:181], v[170:173]
	ds_read_b128 v[178:181], v6 offset:11264
	v_mfma_f32_16x16x32_bf16 v[80:83], v[214:217], v[222:225], v[80:83]
	v_mfma_f32_16x16x32_bf16 v[32:35], v[218:221], v[222:225], v[32:35]
	ds_read_b128 v[222:225], v6 offset:13312
	s_waitcnt lgkmcnt(3)
	v_mfma_f32_16x16x32_bf16 v[88:91], v[158:161], v[226:229], v[88:91]
	v_mfma_f32_16x16x32_bf16 v[92:95], v[162:165], v[226:229], v[92:95]
	v_mfma_f32_16x16x32_bf16 v[96:99], v[214:217], v[226:229], v[96:99]
	v_mfma_f32_16x16x32_bf16 v[36:39], v[218:221], v[226:229], v[36:39]
	ds_read_b128 v[226:229], v6 offset:15360
	s_waitcnt lgkmcnt(3)
	v_mfma_f32_16x16x32_bf16 v[104:107], v[158:161], v[166:169], v[104:107]
	v_mfma_f32_16x16x32_bf16 v[108:111], v[162:165], v[166:169], v[108:111]
	v_mfma_f32_16x16x32_bf16 v[112:115], v[214:217], v[166:169], v[112:115]
	v_mfma_f32_16x16x32_bf16 v[52:55], v[218:221], v[166:169], v[52:55]
	s_waitcnt lgkmcnt(2)
	v_mfma_f32_16x16x32_bf16 v[116:119], v[158:161], v[178:181], v[116:119]
	v_mfma_f32_16x16x32_bf16 v[120:123], v[162:165], v[178:181], v[120:123]
	v_mfma_f32_16x16x32_bf16 v[124:127], v[214:217], v[178:181], v[124:127]
	v_mfma_f32_16x16x32_bf16 v[68:71], v[218:221], v[178:181], v[68:71]
	s_waitcnt lgkmcnt(1)
	v_mfma_f32_16x16x32_bf16 v[128:131], v[158:161], v[222:225], v[128:131]
	v_mfma_f32_16x16x32_bf16 v[132:135], v[162:165], v[222:225], v[132:135]
	v_mfma_f32_16x16x32_bf16 v[136:139], v[214:217], v[222:225], v[136:139]
	v_mfma_f32_16x16x32_bf16 v[84:87], v[218:221], v[222:225], v[84:87]
	s_waitcnt lgkmcnt(0)
	v_mfma_f32_16x16x32_bf16 v[100:103], v[158:161], v[226:229], v[100:103]
	v_mfma_f32_16x16x32_bf16 v[140:143], v[162:165], v[226:229], v[140:143]
	v_mfma_f32_16x16x32_bf16 v[150:153], v[214:217], v[226:229], v[150:153]
	v_mfma_f32_16x16x32_bf16 v[154:157], v[218:221], v[226:229], v[154:157]
	s_add_u32 s64, s0, 0x2b00
	s_addc_u32 s65, s1, 0
	s_add_u32 s68, s14, 0x2b00
	s_waitcnt vmcnt(0)
	s_barrier
	s_addc_u32 s69, s15, 0
	ds_read_b128 v[158:161], v8
	ds_read_b128 v[162:165], v12
	ds_read_b128 v[166:169], v9
	ds_read_b128 v[178:181], v13
	ds_read_b128 v[214:217], v11
	ds_read_b128 v[218:221], v10
	ds_read_b128 v[222:225], v14
	ds_read_b128 v[226:229], v15
	s_waitcnt lgkmcnt(6)
	v_mfma_f32_16x16x32_bf16 v[40:43], v[158:161], v[162:165], v[40:43]
	s_waitcnt lgkmcnt(5)
	v_mfma_f32_16x16x32_bf16 v[44:47], v[166:169], v[162:165], v[44:47]
	s_waitcnt lgkmcnt(4)
	v_mfma_f32_16x16x32_bf16 v[56:59], v[158:161], v[178:181], v[56:59]
	s_mov_b32 m0, s42
	v_mfma_f32_16x16x32_bf16 v[60:63], v[166:169], v[178:181], v[60:63]
	global_load_lds_dwordx4 v0, s[64:65]
	s_waitcnt lgkmcnt(3)
	v_mfma_f32_16x16x32_bf16 v[48:51], v[214:217], v[162:165], v[48:51]
	v_mfma_f32_16x16x32_bf16 v[64:67], v[214:217], v[178:181], v[64:67]
	s_waitcnt lgkmcnt(2)
	v_mfma_f32_16x16x32_bf16 v[174:177], v[218:221], v[162:165], v[174:177]
	ds_read_b128 v[162:165], v16
	v_mfma_f32_16x16x32_bf16 v[170:173], v[218:221], v[178:181], v[170:173]
	ds_read_b128 v[178:181], v17
	s_waitcnt lgkmcnt(3)
	s_mov_b32 m0, s43
	v_mfma_f32_16x16x32_bf16 v[72:75], v[158:161], v[222:225], v[72:75]
	global_load_lds_dwordx4 v0, s[68:69]
	v_mfma_f32_16x16x32_bf16 v[76:79], v[166:169], v[222:225], v[76:79]
	v_mfma_f32_16x16x32_bf16 v[80:83], v[214:217], v[222:225], v[80:83]
	v_mfma_f32_16x16x32_bf16 v[32:35], v[218:221], v[222:225], v[32:35]
	ds_read_b128 v[222:225], v18
	s_waitcnt lgkmcnt(3)
	v_mfma_f32_16x16x32_bf16 v[88:91], v[158:161], v[226:229], v[88:91]
	s_mov_b32 m0, s44
	v_mfma_f32_16x16x32_bf16 v[92:95], v[166:169], v[226:229], v[92:95]
	global_load_lds_dwordx4 v2, s[64:65]
	v_mfma_f32_16x16x32_bf16 v[96:99], v[214:217], v[226:229], v[96:99]
	v_mfma_f32_16x16x32_bf16 v[36:39], v[218:221], v[226:229], v[36:39]
	ds_read_b128 v[226:229], v19
	s_waitcnt lgkmcnt(3)
	v_mfma_f32_16x16x32_bf16 v[104:107], v[158:161], v[162:165], v[104:107]
	s_waitcnt lgkmcnt(2)
	v_mfma_f32_16x16x32_bf16 v[116:119], v[158:161], v[178:181], v[116:119]
	s_waitcnt lgkmcnt(1)
	s_mov_b32 m0, s45
	v_mfma_f32_16x16x32_bf16 v[128:131], v[158:161], v[222:225], v[128:131]
	global_load_lds_dwordx4 v2, s[68:69]
	s_waitcnt lgkmcnt(0)
	v_mfma_f32_16x16x32_bf16 v[100:103], v[158:161], v[226:229], v[100:103]
	ds_read_b128 v[158:161], v20
	v_mfma_f32_16x16x32_bf16 v[108:111], v[166:169], v[162:165], v[108:111]
	v_mfma_f32_16x16x32_bf16 v[120:123], v[166:169], v[178:181], v[120:123]
	v_mfma_f32_16x16x32_bf16 v[132:135], v[166:169], v[222:225], v[132:135]
	s_mov_b32 m0, s46
	v_mfma_f32_16x16x32_bf16 v[140:143], v[166:169], v[226:229], v[140:143]
	global_load_lds_dwordx4 v4, s[64:65]
	ds_read_b128 v[166:169], v24
	v_mfma_f32_16x16x32_bf16 v[112:115], v[214:217], v[162:165], v[112:115]
	v_mfma_f32_16x16x32_bf16 v[52:55], v[218:221], v[162:165], v[52:55]
	ds_read_b128 v[162:165], v21
	v_mfma_f32_16x16x32_bf16 v[124:127], v[214:217], v[178:181], v[124:127]
	v_mfma_f32_16x16x32_bf16 v[68:71], v[218:221], v[178:181], v[68:71]
	ds_read_b128 v[178:181], v25
	s_mov_b32 m0, s47
	v_mfma_f32_16x16x32_bf16 v[136:139], v[214:217], v[222:225], v[136:139]
	global_load_lds_dwordx4 v4, s[68:69]
	v_mfma_f32_16x16x32_bf16 v[84:87], v[218:221], v[222:225], v[84:87]
	ds_read_b128 v[222:225], v26
	v_mfma_f32_16x16x32_bf16 v[150:153], v[214:217], v[226:229], v[150:153]
	ds_read_b128 v[214:217], v23
	v_mfma_f32_16x16x32_bf16 v[154:157], v[218:221], v[226:229], v[154:157]
	ds_read_b128 v[218:221], v22
	ds_read_b128 v[226:229], v27
	s_waitcnt lgkmcnt(6)
	v_mfma_f32_16x16x32_bf16 v[40:43], v[158:161], v[166:169], v[40:43]
	s_waitcnt lgkmcnt(5)
	s_mov_b32 m0, s49
	v_mfma_f32_16x16x32_bf16 v[44:47], v[162:165], v[166:169], v[44:47]
	global_load_lds_dwordx4 v146, s[64:65]
	s_waitcnt lgkmcnt(4)
	v_mfma_f32_16x16x32_bf16 v[56:59], v[158:161], v[178:181], v[56:59]
	v_mfma_f32_16x16x32_bf16 v[60:63], v[162:165], v[178:181], v[60:63]
	s_waitcnt lgkmcnt(3)
	v_mfma_f32_16x16x32_bf16 v[72:75], v[158:161], v[222:225], v[72:75]
	v_mfma_f32_16x16x32_bf16 v[76:79], v[162:165], v[222:225], v[76:79]
	s_waitcnt lgkmcnt(2)
	s_mov_b32 m0, s50
	v_mfma_f32_16x16x32_bf16 v[48:51], v[214:217], v[166:169], v[48:51]
	global_load_lds_dwordx4 v146, s[68:69]
	s_waitcnt lgkmcnt(1)
	v_mfma_f32_16x16x32_bf16 v[174:177], v[218:221], v[166:169], v[174:177]
	ds_read_b128 v[166:169], v28
	v_mfma_f32_16x16x32_bf16 v[64:67], v[214:217], v[178:181], v[64:67]
	v_mfma_f32_16x16x32_bf16 v[170:173], v[218:221], v[178:181], v[170:173]
	ds_read_b128 v[178:181], v29
	v_mfma_f32_16x16x32_bf16 v[80:83], v[214:217], v[222:225], v[80:83]
	v_mfma_f32_16x16x32_bf16 v[32:35], v[218:221], v[222:225], v[32:35]
	ds_read_b128 v[222:225], v30
	s_waitcnt lgkmcnt(3)
	v_mfma_f32_16x16x32_bf16 v[88:91], v[158:161], v[226:229], v[88:91]
	v_mfma_f32_16x16x32_bf16 v[92:95], v[162:165], v[226:229], v[92:95]
	v_mfma_f32_16x16x32_bf16 v[96:99], v[214:217], v[226:229], v[96:99]
	v_mfma_f32_16x16x32_bf16 v[36:39], v[218:221], v[226:229], v[36:39]
	ds_read_b128 v[226:229], v31
	s_waitcnt lgkmcnt(3)
	v_mfma_f32_16x16x32_bf16 v[104:107], v[158:161], v[166:169], v[104:107]
	v_mfma_f32_16x16x32_bf16 v[108:111], v[162:165], v[166:169], v[108:111]
	v_mfma_f32_16x16x32_bf16 v[112:115], v[214:217], v[166:169], v[112:115]
	v_mfma_f32_16x16x32_bf16 v[52:55], v[218:221], v[166:169], v[52:55]
	s_waitcnt lgkmcnt(2)
	v_mfma_f32_16x16x32_bf16 v[116:119], v[158:161], v[178:181], v[116:119]
	v_mfma_f32_16x16x32_bf16 v[120:123], v[162:165], v[178:181], v[120:123]
	v_mfma_f32_16x16x32_bf16 v[124:127], v[214:217], v[178:181], v[124:127]
	v_mfma_f32_16x16x32_bf16 v[68:71], v[218:221], v[178:181], v[68:71]
	s_waitcnt lgkmcnt(1)
	v_mfma_f32_16x16x32_bf16 v[128:131], v[158:161], v[222:225], v[128:131]
	v_mfma_f32_16x16x32_bf16 v[132:135], v[162:165], v[222:225], v[132:135]
	v_mfma_f32_16x16x32_bf16 v[136:139], v[214:217], v[222:225], v[136:139]
	v_mfma_f32_16x16x32_bf16 v[84:87], v[218:221], v[222:225], v[84:87]
	s_waitcnt lgkmcnt(0)
	v_mfma_f32_16x16x32_bf16 v[100:103], v[158:161], v[226:229], v[100:103]
	v_mfma_f32_16x16x32_bf16 v[140:143], v[162:165], v[226:229], v[140:143]
	v_mfma_f32_16x16x32_bf16 v[150:153], v[214:217], v[226:229], v[150:153]
	v_mfma_f32_16x16x32_bf16 v[154:157], v[218:221], v[226:229], v[154:157]
	s_add_u32 s64, s0, 0x2b80
	s_addc_u32 s65, s1, 0
	s_add_u32 s68, s14, 0x2b80
	s_waitcnt vmcnt(0)
	s_barrier
	s_addc_u32 s69, s15, 0
	ds_read_b128 v[158:161], v7 offset:32768
	ds_read_b128 v[162:165], v6
	ds_read_b128 v[166:169], v7 offset:34816
	ds_read_b128 v[178:181], v6 offset:2048
	ds_read_b128 v[214:217], v7 offset:36864
	ds_read_b128 v[218:221], v7 offset:38912
	ds_read_b128 v[222:225], v6 offset:4096
	ds_read_b128 v[226:229], v6 offset:6144
	s_waitcnt lgkmcnt(6)
	v_mfma_f32_16x16x32_bf16 v[40:43], v[158:161], v[162:165], v[40:43]
	s_waitcnt lgkmcnt(5)
	v_mfma_f32_16x16x32_bf16 v[44:47], v[166:169], v[162:165], v[44:47]
	s_waitcnt lgkmcnt(4)
	v_mfma_f32_16x16x32_bf16 v[56:59], v[158:161], v[178:181], v[56:59]
	s_mov_b32 m0, s52
	v_mfma_f32_16x16x32_bf16 v[60:63], v[166:169], v[178:181], v[60:63]
	global_load_lds_dwordx4 v0, s[64:65]
	s_waitcnt lgkmcnt(3)
	v_mfma_f32_16x16x32_bf16 v[48:51], v[214:217], v[162:165], v[48:51]
	v_mfma_f32_16x16x32_bf16 v[64:67], v[214:217], v[178:181], v[64:67]
	s_waitcnt lgkmcnt(2)
	v_mfma_f32_16x16x32_bf16 v[174:177], v[218:221], v[162:165], v[174:177]
	ds_read_b128 v[162:165], v6 offset:8192
	v_mfma_f32_16x16x32_bf16 v[170:173], v[218:221], v[178:181], v[170:173]
	ds_read_b128 v[178:181], v6 offset:10240
	s_waitcnt lgkmcnt(3)
	s_mov_b32 m0, s51
	v_mfma_f32_16x16x32_bf16 v[72:75], v[158:161], v[222:225], v[72:75]
	global_load_lds_dwordx4 v0, s[68:69]
	v_mfma_f32_16x16x32_bf16 v[76:79], v[166:169], v[222:225], v[76:79]
	v_mfma_f32_16x16x32_bf16 v[80:83], v[214:217], v[222:225], v[80:83]
	v_mfma_f32_16x16x32_bf16 v[32:35], v[218:221], v[222:225], v[32:35]
	ds_read_b128 v[222:225], v6 offset:12288
	s_waitcnt lgkmcnt(3)
	v_mfma_f32_16x16x32_bf16 v[88:91], v[158:161], v[226:229], v[88:91]
	s_mov_b32 m0, s53
	v_mfma_f32_16x16x32_bf16 v[92:95], v[166:169], v[226:229], v[92:95]
	global_load_lds_dwordx4 v2, s[64:65]
	v_mfma_f32_16x16x32_bf16 v[96:99], v[214:217], v[226:229], v[96:99]
	v_mfma_f32_16x16x32_bf16 v[36:39], v[218:221], v[226:229], v[36:39]
	ds_read_b128 v[226:229], v6 offset:14336
	s_waitcnt lgkmcnt(3)
	v_mfma_f32_16x16x32_bf16 v[104:107], v[158:161], v[162:165], v[104:107]
	s_waitcnt lgkmcnt(2)
	v_mfma_f32_16x16x32_bf16 v[116:119], v[158:161], v[178:181], v[116:119]
	s_waitcnt lgkmcnt(1)
	s_mov_b32 m0, s54
	v_mfma_f32_16x16x32_bf16 v[128:131], v[158:161], v[222:225], v[128:131]
	global_load_lds_dwordx4 v2, s[68:69]
	s_waitcnt lgkmcnt(0)
	v_mfma_f32_16x16x32_bf16 v[100:103], v[158:161], v[226:229], v[100:103]
	ds_read_b128 v[158:161], v7 offset:33792
	v_mfma_f32_16x16x32_bf16 v[108:111], v[166:169], v[162:165], v[108:111]
	v_mfma_f32_16x16x32_bf16 v[120:123], v[166:169], v[178:181], v[120:123]
	v_mfma_f32_16x16x32_bf16 v[132:135], v[166:169], v[222:225], v[132:135]
	s_mov_b32 m0, s55
	v_mfma_f32_16x16x32_bf16 v[140:143], v[166:169], v[226:229], v[140:143]
	global_load_lds_dwordx4 v4, s[64:65]
	ds_read_b128 v[166:169], v6 offset:1024
	v_mfma_f32_16x16x32_bf16 v[112:115], v[214:217], v[162:165], v[112:115]
	v_mfma_f32_16x16x32_bf16 v[52:55], v[218:221], v[162:165], v[52:55]
	ds_read_b128 v[162:165], v7 offset:35840
	v_mfma_f32_16x16x32_bf16 v[124:127], v[214:217], v[178:181], v[124:127]
	v_mfma_f32_16x16x32_bf16 v[68:71], v[218:221], v[178:181], v[68:71]
	ds_read_b128 v[178:181], v6 offset:3072
	s_mov_b32 m0, s58
	v_mfma_f32_16x16x32_bf16 v[136:139], v[214:217], v[222:225], v[136:139]
	global_load_lds_dwordx4 v4, s[68:69]
	v_mfma_f32_16x16x32_bf16 v[84:87], v[218:221], v[222:225], v[84:87]
	ds_read_b128 v[222:225], v6 offset:5120
	v_mfma_f32_16x16x32_bf16 v[150:153], v[214:217], v[226:229], v[150:153]
	ds_read_b128 v[214:217], v7 offset:37888
	v_mfma_f32_16x16x32_bf16 v[154:157], v[218:221], v[226:229], v[154:157]
	ds_read_b128 v[218:221], v7 offset:39936
	ds_read_b128 v[226:229], v6 offset:7168
	s_waitcnt lgkmcnt(6)
	v_mfma_f32_16x16x32_bf16 v[40:43], v[158:161], v[166:169], v[40:43]
	s_waitcnt lgkmcnt(5)
	s_mov_b32 m0, s62
	v_mfma_f32_16x16x32_bf16 v[44:47], v[162:165], v[166:169], v[44:47]
	global_load_lds_dwordx4 v146, s[64:65]
	s_waitcnt lgkmcnt(4)
	v_mfma_f32_16x16x32_bf16 v[56:59], v[158:161], v[178:181], v[56:59]
	v_mfma_f32_16x16x32_bf16 v[60:63], v[162:165], v[178:181], v[60:63]
	s_waitcnt lgkmcnt(3)
	v_mfma_f32_16x16x32_bf16 v[72:75], v[158:161], v[222:225], v[72:75]
	v_mfma_f32_16x16x32_bf16 v[76:79], v[162:165], v[222:225], v[76:79]
	s_waitcnt lgkmcnt(2)
	s_mov_b32 m0, s63
	v_mfma_f32_16x16x32_bf16 v[48:51], v[214:217], v[166:169], v[48:51]
	global_load_lds_dwordx4 v146, s[68:69]
	s_waitcnt lgkmcnt(1)
	v_mfma_f32_16x16x32_bf16 v[174:177], v[218:221], v[166:169], v[174:177]
	ds_read_b128 v[166:169], v6 offset:9216
	v_mfma_f32_16x16x32_bf16 v[64:67], v[214:217], v[178:181], v[64:67]
	v_mfma_f32_16x16x32_bf16 v[170:173], v[218:221], v[178:181], v[170:173]
	ds_read_b128 v[178:181], v6 offset:11264
	v_mfma_f32_16x16x32_bf16 v[80:83], v[214:217], v[222:225], v[80:83]
	v_mfma_f32_16x16x32_bf16 v[32:35], v[218:221], v[222:225], v[32:35]
	ds_read_b128 v[222:225], v6 offset:13312
	s_waitcnt lgkmcnt(3)
	v_mfma_f32_16x16x32_bf16 v[88:91], v[158:161], v[226:229], v[88:91]
	v_mfma_f32_16x16x32_bf16 v[92:95], v[162:165], v[226:229], v[92:95]
	v_mfma_f32_16x16x32_bf16 v[96:99], v[214:217], v[226:229], v[96:99]
	v_mfma_f32_16x16x32_bf16 v[36:39], v[218:221], v[226:229], v[36:39]
	ds_read_b128 v[226:229], v6 offset:15360
	s_waitcnt lgkmcnt(3)
	v_mfma_f32_16x16x32_bf16 v[104:107], v[158:161], v[166:169], v[104:107]
	v_mfma_f32_16x16x32_bf16 v[108:111], v[162:165], v[166:169], v[108:111]
	v_mfma_f32_16x16x32_bf16 v[112:115], v[214:217], v[166:169], v[112:115]
	v_mfma_f32_16x16x32_bf16 v[52:55], v[218:221], v[166:169], v[52:55]
	s_waitcnt lgkmcnt(2)
	v_mfma_f32_16x16x32_bf16 v[116:119], v[158:161], v[178:181], v[116:119]
	v_mfma_f32_16x16x32_bf16 v[120:123], v[162:165], v[178:181], v[120:123]
	v_mfma_f32_16x16x32_bf16 v[124:127], v[214:217], v[178:181], v[124:127]
	v_mfma_f32_16x16x32_bf16 v[68:71], v[218:221], v[178:181], v[68:71]
	s_waitcnt lgkmcnt(1)
	v_mfma_f32_16x16x32_bf16 v[128:131], v[158:161], v[222:225], v[128:131]
	v_mfma_f32_16x16x32_bf16 v[132:135], v[162:165], v[222:225], v[132:135]
	v_mfma_f32_16x16x32_bf16 v[136:139], v[214:217], v[222:225], v[136:139]
	v_mfma_f32_16x16x32_bf16 v[84:87], v[218:221], v[222:225], v[84:87]
	s_waitcnt lgkmcnt(0)
	v_mfma_f32_16x16x32_bf16 v[100:103], v[158:161], v[226:229], v[100:103]
	v_mfma_f32_16x16x32_bf16 v[140:143], v[162:165], v[226:229], v[140:143]
	v_mfma_f32_16x16x32_bf16 v[150:153], v[214:217], v[226:229], v[150:153]
	v_mfma_f32_16x16x32_bf16 v[154:157], v[218:221], v[226:229], v[154:157]
	s_add_u32 s64, s0, 0x2c00
	s_addc_u32 s65, s1, 0
	s_add_u32 s68, s14, 0x2c00
	s_waitcnt vmcnt(0)
	s_barrier
	s_addc_u32 s69, s15, 0
	ds_read_b128 v[158:161], v8
	ds_read_b128 v[162:165], v12
	ds_read_b128 v[166:169], v9
	ds_read_b128 v[178:181], v13
	ds_read_b128 v[214:217], v11
	ds_read_b128 v[218:221], v10
	ds_read_b128 v[222:225], v14
	ds_read_b128 v[226:229], v15
	s_waitcnt lgkmcnt(6)
	v_mfma_f32_16x16x32_bf16 v[40:43], v[158:161], v[162:165], v[40:43]
	s_waitcnt lgkmcnt(5)
	v_mfma_f32_16x16x32_bf16 v[44:47], v[166:169], v[162:165], v[44:47]
	s_waitcnt lgkmcnt(4)
	v_mfma_f32_16x16x32_bf16 v[56:59], v[158:161], v[178:181], v[56:59]
	s_mov_b32 m0, s42
	v_mfma_f32_16x16x32_bf16 v[60:63], v[166:169], v[178:181], v[60:63]
	global_load_lds_dwordx4 v0, s[64:65]
	s_waitcnt lgkmcnt(3)
	v_mfma_f32_16x16x32_bf16 v[48:51], v[214:217], v[162:165], v[48:51]
	v_mfma_f32_16x16x32_bf16 v[64:67], v[214:217], v[178:181], v[64:67]
	s_waitcnt lgkmcnt(2)
	v_mfma_f32_16x16x32_bf16 v[174:177], v[218:221], v[162:165], v[174:177]
	ds_read_b128 v[162:165], v16
	v_mfma_f32_16x16x32_bf16 v[170:173], v[218:221], v[178:181], v[170:173]
	ds_read_b128 v[178:181], v17
	s_waitcnt lgkmcnt(3)
	s_mov_b32 m0, s43
	v_mfma_f32_16x16x32_bf16 v[72:75], v[158:161], v[222:225], v[72:75]
	global_load_lds_dwordx4 v0, s[68:69]
	v_mfma_f32_16x16x32_bf16 v[76:79], v[166:169], v[222:225], v[76:79]
	v_mfma_f32_16x16x32_bf16 v[80:83], v[214:217], v[222:225], v[80:83]
	v_mfma_f32_16x16x32_bf16 v[32:35], v[218:221], v[222:225], v[32:35]
	ds_read_b128 v[222:225], v18
	s_waitcnt lgkmcnt(3)
	v_mfma_f32_16x16x32_bf16 v[88:91], v[158:161], v[226:229], v[88:91]
	s_mov_b32 m0, s44
	v_mfma_f32_16x16x32_bf16 v[92:95], v[166:169], v[226:229], v[92:95]
	global_load_lds_dwordx4 v2, s[64:65]
	v_mfma_f32_16x16x32_bf16 v[96:99], v[214:217], v[226:229], v[96:99]
	v_mfma_f32_16x16x32_bf16 v[36:39], v[218:221], v[226:229], v[36:39]
	ds_read_b128 v[226:229], v19
	s_waitcnt lgkmcnt(3)
	v_mfma_f32_16x16x32_bf16 v[104:107], v[158:161], v[162:165], v[104:107]
	s_waitcnt lgkmcnt(2)
	v_mfma_f32_16x16x32_bf16 v[116:119], v[158:161], v[178:181], v[116:119]
	s_waitcnt lgkmcnt(1)
	s_mov_b32 m0, s45
	v_mfma_f32_16x16x32_bf16 v[128:131], v[158:161], v[222:225], v[128:131]
	global_load_lds_dwordx4 v2, s[68:69]
	s_waitcnt lgkmcnt(0)
	v_mfma_f32_16x16x32_bf16 v[100:103], v[158:161], v[226:229], v[100:103]
	ds_read_b128 v[158:161], v20
	v_mfma_f32_16x16x32_bf16 v[108:111], v[166:169], v[162:165], v[108:111]
	v_mfma_f32_16x16x32_bf16 v[120:123], v[166:169], v[178:181], v[120:123]
	v_mfma_f32_16x16x32_bf16 v[132:135], v[166:169], v[222:225], v[132:135]
	s_mov_b32 m0, s46
	v_mfma_f32_16x16x32_bf16 v[140:143], v[166:169], v[226:229], v[140:143]
	global_load_lds_dwordx4 v4, s[64:65]
	ds_read_b128 v[166:169], v24
	v_mfma_f32_16x16x32_bf16 v[112:115], v[214:217], v[162:165], v[112:115]
	v_mfma_f32_16x16x32_bf16 v[52:55], v[218:221], v[162:165], v[52:55]
	ds_read_b128 v[162:165], v21
	v_mfma_f32_16x16x32_bf16 v[124:127], v[214:217], v[178:181], v[124:127]
	v_mfma_f32_16x16x32_bf16 v[68:71], v[218:221], v[178:181], v[68:71]
	ds_read_b128 v[178:181], v25
	s_mov_b32 m0, s47
	v_mfma_f32_16x16x32_bf16 v[136:139], v[214:217], v[222:225], v[136:139]
	global_load_lds_dwordx4 v4, s[68:69]
	v_mfma_f32_16x16x32_bf16 v[84:87], v[218:221], v[222:225], v[84:87]
	ds_read_b128 v[222:225], v26
	v_mfma_f32_16x16x32_bf16 v[150:153], v[214:217], v[226:229], v[150:153]
	ds_read_b128 v[214:217], v23
	v_mfma_f32_16x16x32_bf16 v[154:157], v[218:221], v[226:229], v[154:157]
	ds_read_b128 v[218:221], v22
	ds_read_b128 v[226:229], v27
	s_waitcnt lgkmcnt(6)
	v_mfma_f32_16x16x32_bf16 v[40:43], v[158:161], v[166:169], v[40:43]
	s_waitcnt lgkmcnt(5)
	s_mov_b32 m0, s49
	v_mfma_f32_16x16x32_bf16 v[44:47], v[162:165], v[166:169], v[44:47]
	global_load_lds_dwordx4 v146, s[64:65]
	s_waitcnt lgkmcnt(4)
	v_mfma_f32_16x16x32_bf16 v[56:59], v[158:161], v[178:181], v[56:59]
	v_mfma_f32_16x16x32_bf16 v[60:63], v[162:165], v[178:181], v[60:63]
	s_waitcnt lgkmcnt(3)
	v_mfma_f32_16x16x32_bf16 v[72:75], v[158:161], v[222:225], v[72:75]
	v_mfma_f32_16x16x32_bf16 v[76:79], v[162:165], v[222:225], v[76:79]
	s_waitcnt lgkmcnt(2)
	s_mov_b32 m0, s50
	v_mfma_f32_16x16x32_bf16 v[48:51], v[214:217], v[166:169], v[48:51]
	global_load_lds_dwordx4 v146, s[68:69]
	s_waitcnt lgkmcnt(1)
	v_mfma_f32_16x16x32_bf16 v[174:177], v[218:221], v[166:169], v[174:177]
	ds_read_b128 v[166:169], v28
	v_mfma_f32_16x16x32_bf16 v[64:67], v[214:217], v[178:181], v[64:67]
	v_mfma_f32_16x16x32_bf16 v[170:173], v[218:221], v[178:181], v[170:173]
	ds_read_b128 v[178:181], v29
	v_mfma_f32_16x16x32_bf16 v[80:83], v[214:217], v[222:225], v[80:83]
	v_mfma_f32_16x16x32_bf16 v[32:35], v[218:221], v[222:225], v[32:35]
	ds_read_b128 v[222:225], v30
	s_waitcnt lgkmcnt(3)
	v_mfma_f32_16x16x32_bf16 v[88:91], v[158:161], v[226:229], v[88:91]
	v_mfma_f32_16x16x32_bf16 v[92:95], v[162:165], v[226:229], v[92:95]
	v_mfma_f32_16x16x32_bf16 v[96:99], v[214:217], v[226:229], v[96:99]
	v_mfma_f32_16x16x32_bf16 v[36:39], v[218:221], v[226:229], v[36:39]
	ds_read_b128 v[226:229], v31
	s_waitcnt lgkmcnt(3)
	v_mfma_f32_16x16x32_bf16 v[104:107], v[158:161], v[166:169], v[104:107]
	v_mfma_f32_16x16x32_bf16 v[108:111], v[162:165], v[166:169], v[108:111]
	v_mfma_f32_16x16x32_bf16 v[112:115], v[214:217], v[166:169], v[112:115]
	v_mfma_f32_16x16x32_bf16 v[52:55], v[218:221], v[166:169], v[52:55]
	s_waitcnt lgkmcnt(2)
	v_mfma_f32_16x16x32_bf16 v[116:119], v[158:161], v[178:181], v[116:119]
	v_mfma_f32_16x16x32_bf16 v[120:123], v[162:165], v[178:181], v[120:123]
	v_mfma_f32_16x16x32_bf16 v[124:127], v[214:217], v[178:181], v[124:127]
	v_mfma_f32_16x16x32_bf16 v[68:71], v[218:221], v[178:181], v[68:71]
	s_waitcnt lgkmcnt(1)
	v_mfma_f32_16x16x32_bf16 v[128:131], v[158:161], v[222:225], v[128:131]
	v_mfma_f32_16x16x32_bf16 v[132:135], v[162:165], v[222:225], v[132:135]
	v_mfma_f32_16x16x32_bf16 v[136:139], v[214:217], v[222:225], v[136:139]
	v_mfma_f32_16x16x32_bf16 v[84:87], v[218:221], v[222:225], v[84:87]
	s_waitcnt lgkmcnt(0)
	v_mfma_f32_16x16x32_bf16 v[100:103], v[158:161], v[226:229], v[100:103]
	v_mfma_f32_16x16x32_bf16 v[140:143], v[162:165], v[226:229], v[140:143]
	v_mfma_f32_16x16x32_bf16 v[150:153], v[214:217], v[226:229], v[150:153]
	v_mfma_f32_16x16x32_bf16 v[154:157], v[218:221], v[226:229], v[154:157]
	s_add_u32 s64, s0, 0x2c80
	s_addc_u32 s65, s1, 0
	s_add_u32 s68, s14, 0x2c80
	s_waitcnt vmcnt(0)
	s_barrier
	s_addc_u32 s69, s15, 0
	ds_read_b128 v[158:161], v7 offset:32768
	ds_read_b128 v[162:165], v6
	ds_read_b128 v[166:169], v7 offset:34816
	ds_read_b128 v[178:181], v6 offset:2048
	ds_read_b128 v[214:217], v7 offset:36864
	ds_read_b128 v[218:221], v7 offset:38912
	ds_read_b128 v[222:225], v6 offset:4096
	ds_read_b128 v[226:229], v6 offset:6144
	s_waitcnt lgkmcnt(6)
	v_mfma_f32_16x16x32_bf16 v[40:43], v[158:161], v[162:165], v[40:43]
	s_waitcnt lgkmcnt(5)
	v_mfma_f32_16x16x32_bf16 v[44:47], v[166:169], v[162:165], v[44:47]
	s_waitcnt lgkmcnt(4)
	v_mfma_f32_16x16x32_bf16 v[56:59], v[158:161], v[178:181], v[56:59]
	s_mov_b32 m0, s52
	v_mfma_f32_16x16x32_bf16 v[60:63], v[166:169], v[178:181], v[60:63]
	global_load_lds_dwordx4 v0, s[64:65]
	s_waitcnt lgkmcnt(3)
	v_mfma_f32_16x16x32_bf16 v[48:51], v[214:217], v[162:165], v[48:51]
	v_mfma_f32_16x16x32_bf16 v[64:67], v[214:217], v[178:181], v[64:67]
	s_waitcnt lgkmcnt(2)
	v_mfma_f32_16x16x32_bf16 v[174:177], v[218:221], v[162:165], v[174:177]
	ds_read_b128 v[162:165], v6 offset:8192
	v_mfma_f32_16x16x32_bf16 v[170:173], v[218:221], v[178:181], v[170:173]
	ds_read_b128 v[178:181], v6 offset:10240
	s_waitcnt lgkmcnt(3)
	s_mov_b32 m0, s51
	v_mfma_f32_16x16x32_bf16 v[72:75], v[158:161], v[222:225], v[72:75]
	global_load_lds_dwordx4 v0, s[68:69]
	v_mfma_f32_16x16x32_bf16 v[76:79], v[166:169], v[222:225], v[76:79]
	v_mfma_f32_16x16x32_bf16 v[80:83], v[214:217], v[222:225], v[80:83]
	v_mfma_f32_16x16x32_bf16 v[32:35], v[218:221], v[222:225], v[32:35]
	ds_read_b128 v[222:225], v6 offset:12288
	s_waitcnt lgkmcnt(3)
	v_mfma_f32_16x16x32_bf16 v[88:91], v[158:161], v[226:229], v[88:91]
	s_mov_b32 m0, s53
	v_mfma_f32_16x16x32_bf16 v[92:95], v[166:169], v[226:229], v[92:95]
	global_load_lds_dwordx4 v2, s[64:65]
	v_mfma_f32_16x16x32_bf16 v[96:99], v[214:217], v[226:229], v[96:99]
	v_mfma_f32_16x16x32_bf16 v[36:39], v[218:221], v[226:229], v[36:39]
	ds_read_b128 v[226:229], v6 offset:14336
	s_waitcnt lgkmcnt(3)
	v_mfma_f32_16x16x32_bf16 v[104:107], v[158:161], v[162:165], v[104:107]
	s_waitcnt lgkmcnt(2)
	v_mfma_f32_16x16x32_bf16 v[116:119], v[158:161], v[178:181], v[116:119]
	s_waitcnt lgkmcnt(1)
	s_mov_b32 m0, s54
	v_mfma_f32_16x16x32_bf16 v[128:131], v[158:161], v[222:225], v[128:131]
	global_load_lds_dwordx4 v2, s[68:69]
	s_waitcnt lgkmcnt(0)
	v_mfma_f32_16x16x32_bf16 v[100:103], v[158:161], v[226:229], v[100:103]
	ds_read_b128 v[158:161], v7 offset:33792
	v_mfma_f32_16x16x32_bf16 v[108:111], v[166:169], v[162:165], v[108:111]
	v_mfma_f32_16x16x32_bf16 v[120:123], v[166:169], v[178:181], v[120:123]
	v_mfma_f32_16x16x32_bf16 v[132:135], v[166:169], v[222:225], v[132:135]
	s_mov_b32 m0, s55
	v_mfma_f32_16x16x32_bf16 v[140:143], v[166:169], v[226:229], v[140:143]
	global_load_lds_dwordx4 v4, s[64:65]
	ds_read_b128 v[166:169], v6 offset:1024
	v_mfma_f32_16x16x32_bf16 v[112:115], v[214:217], v[162:165], v[112:115]
	v_mfma_f32_16x16x32_bf16 v[52:55], v[218:221], v[162:165], v[52:55]
	ds_read_b128 v[162:165], v7 offset:35840
	v_mfma_f32_16x16x32_bf16 v[124:127], v[214:217], v[178:181], v[124:127]
	v_mfma_f32_16x16x32_bf16 v[68:71], v[218:221], v[178:181], v[68:71]
	ds_read_b128 v[178:181], v6 offset:3072
	s_mov_b32 m0, s58
	v_mfma_f32_16x16x32_bf16 v[136:139], v[214:217], v[222:225], v[136:139]
	global_load_lds_dwordx4 v4, s[68:69]
	v_mfma_f32_16x16x32_bf16 v[84:87], v[218:221], v[222:225], v[84:87]
	ds_read_b128 v[222:225], v6 offset:5120
	v_mfma_f32_16x16x32_bf16 v[150:153], v[214:217], v[226:229], v[150:153]
	ds_read_b128 v[214:217], v7 offset:37888
	v_mfma_f32_16x16x32_bf16 v[154:157], v[218:221], v[226:229], v[154:157]
	ds_read_b128 v[218:221], v7 offset:39936
	ds_read_b128 v[226:229], v6 offset:7168
	s_waitcnt lgkmcnt(6)
	v_mfma_f32_16x16x32_bf16 v[40:43], v[158:161], v[166:169], v[40:43]
	s_waitcnt lgkmcnt(5)
	s_mov_b32 m0, s62
	v_mfma_f32_16x16x32_bf16 v[44:47], v[162:165], v[166:169], v[44:47]
	global_load_lds_dwordx4 v146, s[64:65]
	s_waitcnt lgkmcnt(4)
	v_mfma_f32_16x16x32_bf16 v[56:59], v[158:161], v[178:181], v[56:59]
	v_mfma_f32_16x16x32_bf16 v[60:63], v[162:165], v[178:181], v[60:63]
	s_waitcnt lgkmcnt(3)
	v_mfma_f32_16x16x32_bf16 v[72:75], v[158:161], v[222:225], v[72:75]
	v_mfma_f32_16x16x32_bf16 v[76:79], v[162:165], v[222:225], v[76:79]
	s_waitcnt lgkmcnt(2)
	s_mov_b32 m0, s63
	v_mfma_f32_16x16x32_bf16 v[48:51], v[214:217], v[166:169], v[48:51]
	global_load_lds_dwordx4 v146, s[68:69]
	s_waitcnt lgkmcnt(1)
	v_mfma_f32_16x16x32_bf16 v[174:177], v[218:221], v[166:169], v[174:177]
	ds_read_b128 v[166:169], v6 offset:9216
	v_mfma_f32_16x16x32_bf16 v[64:67], v[214:217], v[178:181], v[64:67]
	v_mfma_f32_16x16x32_bf16 v[170:173], v[218:221], v[178:181], v[170:173]
	ds_read_b128 v[178:181], v6 offset:11264
	v_mfma_f32_16x16x32_bf16 v[80:83], v[214:217], v[222:225], v[80:83]
	v_mfma_f32_16x16x32_bf16 v[32:35], v[218:221], v[222:225], v[32:35]
	ds_read_b128 v[222:225], v6 offset:13312
	s_waitcnt lgkmcnt(3)
	v_mfma_f32_16x16x32_bf16 v[88:91], v[158:161], v[226:229], v[88:91]
	v_mfma_f32_16x16x32_bf16 v[92:95], v[162:165], v[226:229], v[92:95]
	v_mfma_f32_16x16x32_bf16 v[96:99], v[214:217], v[226:229], v[96:99]
	v_mfma_f32_16x16x32_bf16 v[36:39], v[218:221], v[226:229], v[36:39]
	ds_read_b128 v[226:229], v6 offset:15360
	s_waitcnt lgkmcnt(3)
	v_mfma_f32_16x16x32_bf16 v[104:107], v[158:161], v[166:169], v[104:107]
	v_mfma_f32_16x16x32_bf16 v[108:111], v[162:165], v[166:169], v[108:111]
	v_mfma_f32_16x16x32_bf16 v[112:115], v[214:217], v[166:169], v[112:115]
	v_mfma_f32_16x16x32_bf16 v[52:55], v[218:221], v[166:169], v[52:55]
	s_waitcnt lgkmcnt(2)
	v_mfma_f32_16x16x32_bf16 v[116:119], v[158:161], v[178:181], v[116:119]
	v_mfma_f32_16x16x32_bf16 v[120:123], v[162:165], v[178:181], v[120:123]
	v_mfma_f32_16x16x32_bf16 v[124:127], v[214:217], v[178:181], v[124:127]
	v_mfma_f32_16x16x32_bf16 v[68:71], v[218:221], v[178:181], v[68:71]
	s_waitcnt lgkmcnt(1)
	v_mfma_f32_16x16x32_bf16 v[128:131], v[158:161], v[222:225], v[128:131]
	v_mfma_f32_16x16x32_bf16 v[132:135], v[162:165], v[222:225], v[132:135]
	v_mfma_f32_16x16x32_bf16 v[136:139], v[214:217], v[222:225], v[136:139]
	v_mfma_f32_16x16x32_bf16 v[84:87], v[218:221], v[222:225], v[84:87]
	s_waitcnt lgkmcnt(0)
	v_mfma_f32_16x16x32_bf16 v[100:103], v[158:161], v[226:229], v[100:103]
	v_mfma_f32_16x16x32_bf16 v[140:143], v[162:165], v[226:229], v[140:143]
	v_mfma_f32_16x16x32_bf16 v[150:153], v[214:217], v[226:229], v[150:153]
	v_mfma_f32_16x16x32_bf16 v[154:157], v[218:221], v[226:229], v[154:157]
	s_add_u32 s64, s0, 0x2d00
	s_addc_u32 s65, s1, 0
	s_add_u32 s68, s14, 0x2d00
	s_waitcnt vmcnt(0)
	s_barrier
	s_addc_u32 s69, s15, 0
	ds_read_b128 v[158:161], v8
	ds_read_b128 v[162:165], v12
	ds_read_b128 v[166:169], v9
	ds_read_b128 v[178:181], v13
	ds_read_b128 v[214:217], v11
	ds_read_b128 v[218:221], v10
	ds_read_b128 v[222:225], v14
	ds_read_b128 v[226:229], v15
	s_waitcnt lgkmcnt(6)
	v_mfma_f32_16x16x32_bf16 v[40:43], v[158:161], v[162:165], v[40:43]
	s_waitcnt lgkmcnt(5)
	v_mfma_f32_16x16x32_bf16 v[44:47], v[166:169], v[162:165], v[44:47]
	s_waitcnt lgkmcnt(4)
	v_mfma_f32_16x16x32_bf16 v[56:59], v[158:161], v[178:181], v[56:59]
	s_mov_b32 m0, s42
	v_mfma_f32_16x16x32_bf16 v[60:63], v[166:169], v[178:181], v[60:63]
	global_load_lds_dwordx4 v0, s[64:65]
	s_waitcnt lgkmcnt(3)
	v_mfma_f32_16x16x32_bf16 v[48:51], v[214:217], v[162:165], v[48:51]
	v_mfma_f32_16x16x32_bf16 v[64:67], v[214:217], v[178:181], v[64:67]
	s_waitcnt lgkmcnt(2)
	v_mfma_f32_16x16x32_bf16 v[174:177], v[218:221], v[162:165], v[174:177]
	ds_read_b128 v[162:165], v16
	v_mfma_f32_16x16x32_bf16 v[170:173], v[218:221], v[178:181], v[170:173]
	ds_read_b128 v[178:181], v17
	s_waitcnt lgkmcnt(3)
	s_mov_b32 m0, s43
	v_mfma_f32_16x16x32_bf16 v[72:75], v[158:161], v[222:225], v[72:75]
	global_load_lds_dwordx4 v0, s[68:69]
	v_mfma_f32_16x16x32_bf16 v[76:79], v[166:169], v[222:225], v[76:79]
	v_mfma_f32_16x16x32_bf16 v[80:83], v[214:217], v[222:225], v[80:83]
	v_mfma_f32_16x16x32_bf16 v[32:35], v[218:221], v[222:225], v[32:35]
	ds_read_b128 v[222:225], v18
	s_waitcnt lgkmcnt(3)
	v_mfma_f32_16x16x32_bf16 v[88:91], v[158:161], v[226:229], v[88:91]
	s_mov_b32 m0, s44
	v_mfma_f32_16x16x32_bf16 v[92:95], v[166:169], v[226:229], v[92:95]
	global_load_lds_dwordx4 v2, s[64:65]
	v_mfma_f32_16x16x32_bf16 v[96:99], v[214:217], v[226:229], v[96:99]
	v_mfma_f32_16x16x32_bf16 v[36:39], v[218:221], v[226:229], v[36:39]
	ds_read_b128 v[226:229], v19
	s_waitcnt lgkmcnt(3)
	v_mfma_f32_16x16x32_bf16 v[104:107], v[158:161], v[162:165], v[104:107]
	s_waitcnt lgkmcnt(2)
	v_mfma_f32_16x16x32_bf16 v[116:119], v[158:161], v[178:181], v[116:119]
	s_waitcnt lgkmcnt(1)
	s_mov_b32 m0, s45
	v_mfma_f32_16x16x32_bf16 v[128:131], v[158:161], v[222:225], v[128:131]
	global_load_lds_dwordx4 v2, s[68:69]
	s_waitcnt lgkmcnt(0)
	v_mfma_f32_16x16x32_bf16 v[100:103], v[158:161], v[226:229], v[100:103]
	ds_read_b128 v[158:161], v20
	v_mfma_f32_16x16x32_bf16 v[108:111], v[166:169], v[162:165], v[108:111]
	v_mfma_f32_16x16x32_bf16 v[120:123], v[166:169], v[178:181], v[120:123]
	v_mfma_f32_16x16x32_bf16 v[132:135], v[166:169], v[222:225], v[132:135]
	s_mov_b32 m0, s46
	v_mfma_f32_16x16x32_bf16 v[140:143], v[166:169], v[226:229], v[140:143]
	global_load_lds_dwordx4 v4, s[64:65]
	ds_read_b128 v[166:169], v24
	v_mfma_f32_16x16x32_bf16 v[112:115], v[214:217], v[162:165], v[112:115]
	v_mfma_f32_16x16x32_bf16 v[52:55], v[218:221], v[162:165], v[52:55]
	ds_read_b128 v[162:165], v21
	v_mfma_f32_16x16x32_bf16 v[124:127], v[214:217], v[178:181], v[124:127]
	v_mfma_f32_16x16x32_bf16 v[68:71], v[218:221], v[178:181], v[68:71]
	ds_read_b128 v[178:181], v25
	s_mov_b32 m0, s47
	v_mfma_f32_16x16x32_bf16 v[136:139], v[214:217], v[222:225], v[136:139]
	global_load_lds_dwordx4 v4, s[68:69]
	v_mfma_f32_16x16x32_bf16 v[84:87], v[218:221], v[222:225], v[84:87]
	ds_read_b128 v[222:225], v26
	v_mfma_f32_16x16x32_bf16 v[150:153], v[214:217], v[226:229], v[150:153]
	ds_read_b128 v[214:217], v23
	v_mfma_f32_16x16x32_bf16 v[154:157], v[218:221], v[226:229], v[154:157]
	ds_read_b128 v[218:221], v22
	ds_read_b128 v[226:229], v27
	s_waitcnt lgkmcnt(6)
	v_mfma_f32_16x16x32_bf16 v[40:43], v[158:161], v[166:169], v[40:43]
	s_waitcnt lgkmcnt(5)
	s_mov_b32 m0, s49
	v_mfma_f32_16x16x32_bf16 v[44:47], v[162:165], v[166:169], v[44:47]
	global_load_lds_dwordx4 v146, s[64:65]
	s_waitcnt lgkmcnt(4)
	v_mfma_f32_16x16x32_bf16 v[56:59], v[158:161], v[178:181], v[56:59]
	v_mfma_f32_16x16x32_bf16 v[60:63], v[162:165], v[178:181], v[60:63]
	s_waitcnt lgkmcnt(3)
	v_mfma_f32_16x16x32_bf16 v[72:75], v[158:161], v[222:225], v[72:75]
	v_mfma_f32_16x16x32_bf16 v[76:79], v[162:165], v[222:225], v[76:79]
	s_waitcnt lgkmcnt(2)
	s_mov_b32 m0, s50
	v_mfma_f32_16x16x32_bf16 v[48:51], v[214:217], v[166:169], v[48:51]
	global_load_lds_dwordx4 v146, s[68:69]
	s_waitcnt lgkmcnt(1)
	v_mfma_f32_16x16x32_bf16 v[174:177], v[218:221], v[166:169], v[174:177]
	ds_read_b128 v[166:169], v28
	v_mfma_f32_16x16x32_bf16 v[64:67], v[214:217], v[178:181], v[64:67]
	v_mfma_f32_16x16x32_bf16 v[170:173], v[218:221], v[178:181], v[170:173]
	ds_read_b128 v[178:181], v29
	v_mfma_f32_16x16x32_bf16 v[80:83], v[214:217], v[222:225], v[80:83]
	v_mfma_f32_16x16x32_bf16 v[32:35], v[218:221], v[222:225], v[32:35]
	ds_read_b128 v[222:225], v30
	s_waitcnt lgkmcnt(3)
	v_mfma_f32_16x16x32_bf16 v[88:91], v[158:161], v[226:229], v[88:91]
	v_mfma_f32_16x16x32_bf16 v[92:95], v[162:165], v[226:229], v[92:95]
	v_mfma_f32_16x16x32_bf16 v[96:99], v[214:217], v[226:229], v[96:99]
	v_mfma_f32_16x16x32_bf16 v[36:39], v[218:221], v[226:229], v[36:39]
	ds_read_b128 v[226:229], v31
	s_waitcnt lgkmcnt(3)
	v_mfma_f32_16x16x32_bf16 v[104:107], v[158:161], v[166:169], v[104:107]
	v_mfma_f32_16x16x32_bf16 v[108:111], v[162:165], v[166:169], v[108:111]
	v_mfma_f32_16x16x32_bf16 v[112:115], v[214:217], v[166:169], v[112:115]
	v_mfma_f32_16x16x32_bf16 v[52:55], v[218:221], v[166:169], v[52:55]
	s_waitcnt lgkmcnt(2)
	v_mfma_f32_16x16x32_bf16 v[116:119], v[158:161], v[178:181], v[116:119]
	v_mfma_f32_16x16x32_bf16 v[120:123], v[162:165], v[178:181], v[120:123]
	v_mfma_f32_16x16x32_bf16 v[124:127], v[214:217], v[178:181], v[124:127]
	v_mfma_f32_16x16x32_bf16 v[68:71], v[218:221], v[178:181], v[68:71]
	s_waitcnt lgkmcnt(1)
	v_mfma_f32_16x16x32_bf16 v[128:131], v[158:161], v[222:225], v[128:131]
	v_mfma_f32_16x16x32_bf16 v[132:135], v[162:165], v[222:225], v[132:135]
	v_mfma_f32_16x16x32_bf16 v[136:139], v[214:217], v[222:225], v[136:139]
	v_mfma_f32_16x16x32_bf16 v[84:87], v[218:221], v[222:225], v[84:87]
	s_waitcnt lgkmcnt(0)
	v_mfma_f32_16x16x32_bf16 v[100:103], v[158:161], v[226:229], v[100:103]
	v_mfma_f32_16x16x32_bf16 v[140:143], v[162:165], v[226:229], v[140:143]
	v_mfma_f32_16x16x32_bf16 v[150:153], v[214:217], v[226:229], v[150:153]
	v_mfma_f32_16x16x32_bf16 v[154:157], v[218:221], v[226:229], v[154:157]
	s_add_u32 s64, s0, 0x2d80
	s_addc_u32 s65, s1, 0
	s_add_u32 s68, s14, 0x2d80
	s_waitcnt vmcnt(0)
	s_barrier
	s_addc_u32 s69, s15, 0
	ds_read_b128 v[158:161], v7 offset:32768
	ds_read_b128 v[162:165], v6
	ds_read_b128 v[166:169], v7 offset:34816
	ds_read_b128 v[178:181], v6 offset:2048
	ds_read_b128 v[214:217], v7 offset:36864
	ds_read_b128 v[218:221], v7 offset:38912
	ds_read_b128 v[222:225], v6 offset:4096
	ds_read_b128 v[226:229], v6 offset:6144
	s_waitcnt lgkmcnt(6)
	v_mfma_f32_16x16x32_bf16 v[40:43], v[158:161], v[162:165], v[40:43]
	s_waitcnt lgkmcnt(5)
	v_mfma_f32_16x16x32_bf16 v[44:47], v[166:169], v[162:165], v[44:47]
	s_waitcnt lgkmcnt(4)
	v_mfma_f32_16x16x32_bf16 v[56:59], v[158:161], v[178:181], v[56:59]
	s_mov_b32 m0, s52
	v_mfma_f32_16x16x32_bf16 v[60:63], v[166:169], v[178:181], v[60:63]
	global_load_lds_dwordx4 v0, s[64:65]
	s_waitcnt lgkmcnt(3)
	v_mfma_f32_16x16x32_bf16 v[48:51], v[214:217], v[162:165], v[48:51]
	v_mfma_f32_16x16x32_bf16 v[64:67], v[214:217], v[178:181], v[64:67]
	s_waitcnt lgkmcnt(2)
	v_mfma_f32_16x16x32_bf16 v[174:177], v[218:221], v[162:165], v[174:177]
	ds_read_b128 v[162:165], v6 offset:8192
	v_mfma_f32_16x16x32_bf16 v[170:173], v[218:221], v[178:181], v[170:173]
	ds_read_b128 v[178:181], v6 offset:10240
	s_waitcnt lgkmcnt(3)
	s_mov_b32 m0, s51
	v_mfma_f32_16x16x32_bf16 v[72:75], v[158:161], v[222:225], v[72:75]
	global_load_lds_dwordx4 v0, s[68:69]
	v_mfma_f32_16x16x32_bf16 v[76:79], v[166:169], v[222:225], v[76:79]
	v_mfma_f32_16x16x32_bf16 v[80:83], v[214:217], v[222:225], v[80:83]
	v_mfma_f32_16x16x32_bf16 v[32:35], v[218:221], v[222:225], v[32:35]
	ds_read_b128 v[222:225], v6 offset:12288
	s_waitcnt lgkmcnt(3)
	v_mfma_f32_16x16x32_bf16 v[88:91], v[158:161], v[226:229], v[88:91]
	s_mov_b32 m0, s53
	v_mfma_f32_16x16x32_bf16 v[92:95], v[166:169], v[226:229], v[92:95]
	global_load_lds_dwordx4 v2, s[64:65]
	v_mfma_f32_16x16x32_bf16 v[96:99], v[214:217], v[226:229], v[96:99]
	v_mfma_f32_16x16x32_bf16 v[36:39], v[218:221], v[226:229], v[36:39]
	ds_read_b128 v[226:229], v6 offset:14336
	s_waitcnt lgkmcnt(3)
	v_mfma_f32_16x16x32_bf16 v[104:107], v[158:161], v[162:165], v[104:107]
	s_waitcnt lgkmcnt(2)
	v_mfma_f32_16x16x32_bf16 v[116:119], v[158:161], v[178:181], v[116:119]
	s_waitcnt lgkmcnt(1)
	s_mov_b32 m0, s54
	v_mfma_f32_16x16x32_bf16 v[128:131], v[158:161], v[222:225], v[128:131]
	global_load_lds_dwordx4 v2, s[68:69]
	s_waitcnt lgkmcnt(0)
	v_mfma_f32_16x16x32_bf16 v[100:103], v[158:161], v[226:229], v[100:103]
	ds_read_b128 v[158:161], v7 offset:33792
	v_mfma_f32_16x16x32_bf16 v[108:111], v[166:169], v[162:165], v[108:111]
	v_mfma_f32_16x16x32_bf16 v[120:123], v[166:169], v[178:181], v[120:123]
	v_mfma_f32_16x16x32_bf16 v[132:135], v[166:169], v[222:225], v[132:135]
	s_mov_b32 m0, s55
	v_mfma_f32_16x16x32_bf16 v[140:143], v[166:169], v[226:229], v[140:143]
	global_load_lds_dwordx4 v4, s[64:65]
	ds_read_b128 v[166:169], v6 offset:1024
	v_mfma_f32_16x16x32_bf16 v[112:115], v[214:217], v[162:165], v[112:115]
	v_mfma_f32_16x16x32_bf16 v[52:55], v[218:221], v[162:165], v[52:55]
	ds_read_b128 v[162:165], v7 offset:35840
	v_mfma_f32_16x16x32_bf16 v[124:127], v[214:217], v[178:181], v[124:127]
	v_mfma_f32_16x16x32_bf16 v[68:71], v[218:221], v[178:181], v[68:71]
	ds_read_b128 v[178:181], v6 offset:3072
	s_mov_b32 m0, s58
	v_mfma_f32_16x16x32_bf16 v[136:139], v[214:217], v[222:225], v[136:139]
	global_load_lds_dwordx4 v4, s[68:69]
	v_mfma_f32_16x16x32_bf16 v[84:87], v[218:221], v[222:225], v[84:87]
	ds_read_b128 v[222:225], v6 offset:5120
	v_mfma_f32_16x16x32_bf16 v[150:153], v[214:217], v[226:229], v[150:153]
	ds_read_b128 v[214:217], v7 offset:37888
	v_mfma_f32_16x16x32_bf16 v[154:157], v[218:221], v[226:229], v[154:157]
	ds_read_b128 v[218:221], v7 offset:39936
	ds_read_b128 v[226:229], v6 offset:7168
	s_waitcnt lgkmcnt(6)
	v_mfma_f32_16x16x32_bf16 v[40:43], v[158:161], v[166:169], v[40:43]
	s_waitcnt lgkmcnt(5)
	s_mov_b32 m0, s62
	v_mfma_f32_16x16x32_bf16 v[44:47], v[162:165], v[166:169], v[44:47]
	global_load_lds_dwordx4 v146, s[64:65]
	s_waitcnt lgkmcnt(4)
	v_mfma_f32_16x16x32_bf16 v[56:59], v[158:161], v[178:181], v[56:59]
	v_mfma_f32_16x16x32_bf16 v[60:63], v[162:165], v[178:181], v[60:63]
	s_waitcnt lgkmcnt(3)
	v_mfma_f32_16x16x32_bf16 v[72:75], v[158:161], v[222:225], v[72:75]
	v_mfma_f32_16x16x32_bf16 v[76:79], v[162:165], v[222:225], v[76:79]
	s_waitcnt lgkmcnt(2)
	s_mov_b32 m0, s63
	v_mfma_f32_16x16x32_bf16 v[48:51], v[214:217], v[166:169], v[48:51]
	global_load_lds_dwordx4 v146, s[68:69]
	s_waitcnt lgkmcnt(1)
	v_mfma_f32_16x16x32_bf16 v[174:177], v[218:221], v[166:169], v[174:177]
	ds_read_b128 v[166:169], v6 offset:9216
	v_mfma_f32_16x16x32_bf16 v[64:67], v[214:217], v[178:181], v[64:67]
	v_mfma_f32_16x16x32_bf16 v[170:173], v[218:221], v[178:181], v[170:173]
	ds_read_b128 v[178:181], v6 offset:11264
	v_mfma_f32_16x16x32_bf16 v[80:83], v[214:217], v[222:225], v[80:83]
	v_mfma_f32_16x16x32_bf16 v[32:35], v[218:221], v[222:225], v[32:35]
	ds_read_b128 v[222:225], v6 offset:13312
	s_waitcnt lgkmcnt(3)
	v_mfma_f32_16x16x32_bf16 v[88:91], v[158:161], v[226:229], v[88:91]
	v_mfma_f32_16x16x32_bf16 v[92:95], v[162:165], v[226:229], v[92:95]
	v_mfma_f32_16x16x32_bf16 v[96:99], v[214:217], v[226:229], v[96:99]
	v_mfma_f32_16x16x32_bf16 v[36:39], v[218:221], v[226:229], v[36:39]
	ds_read_b128 v[226:229], v6 offset:15360
	s_waitcnt lgkmcnt(3)
	v_mfma_f32_16x16x32_bf16 v[104:107], v[158:161], v[166:169], v[104:107]
	v_mfma_f32_16x16x32_bf16 v[108:111], v[162:165], v[166:169], v[108:111]
	v_mfma_f32_16x16x32_bf16 v[112:115], v[214:217], v[166:169], v[112:115]
	v_mfma_f32_16x16x32_bf16 v[52:55], v[218:221], v[166:169], v[52:55]
	s_waitcnt lgkmcnt(2)
	v_mfma_f32_16x16x32_bf16 v[116:119], v[158:161], v[178:181], v[116:119]
	v_mfma_f32_16x16x32_bf16 v[120:123], v[162:165], v[178:181], v[120:123]
	v_mfma_f32_16x16x32_bf16 v[124:127], v[214:217], v[178:181], v[124:127]
	v_mfma_f32_16x16x32_bf16 v[68:71], v[218:221], v[178:181], v[68:71]
	s_waitcnt lgkmcnt(1)
	v_mfma_f32_16x16x32_bf16 v[128:131], v[158:161], v[222:225], v[128:131]
	v_mfma_f32_16x16x32_bf16 v[132:135], v[162:165], v[222:225], v[132:135]
	v_mfma_f32_16x16x32_bf16 v[136:139], v[214:217], v[222:225], v[136:139]
	v_mfma_f32_16x16x32_bf16 v[84:87], v[218:221], v[222:225], v[84:87]
	s_waitcnt lgkmcnt(0)
	v_mfma_f32_16x16x32_bf16 v[100:103], v[158:161], v[226:229], v[100:103]
	v_mfma_f32_16x16x32_bf16 v[140:143], v[162:165], v[226:229], v[140:143]
	v_mfma_f32_16x16x32_bf16 v[150:153], v[214:217], v[226:229], v[150:153]
	v_mfma_f32_16x16x32_bf16 v[154:157], v[218:221], v[226:229], v[154:157]
	s_add_u32 s64, s0, 0x2e00
	s_addc_u32 s65, s1, 0
	s_add_u32 s68, s14, 0x2e00
	s_waitcnt vmcnt(0)
	s_barrier
	s_addc_u32 s69, s15, 0
	ds_read_b128 v[158:161], v8
	ds_read_b128 v[162:165], v12
	ds_read_b128 v[166:169], v9
	ds_read_b128 v[178:181], v13
	ds_read_b128 v[214:217], v11
	ds_read_b128 v[218:221], v10
	ds_read_b128 v[222:225], v14
	ds_read_b128 v[226:229], v15
	s_waitcnt lgkmcnt(6)
	v_mfma_f32_16x16x32_bf16 v[40:43], v[158:161], v[162:165], v[40:43]
	s_waitcnt lgkmcnt(5)
	v_mfma_f32_16x16x32_bf16 v[44:47], v[166:169], v[162:165], v[44:47]
	s_waitcnt lgkmcnt(4)
	v_mfma_f32_16x16x32_bf16 v[56:59], v[158:161], v[178:181], v[56:59]
	s_mov_b32 m0, s42
	v_mfma_f32_16x16x32_bf16 v[60:63], v[166:169], v[178:181], v[60:63]
	global_load_lds_dwordx4 v0, s[64:65]
	s_waitcnt lgkmcnt(3)
	v_mfma_f32_16x16x32_bf16 v[48:51], v[214:217], v[162:165], v[48:51]
	v_mfma_f32_16x16x32_bf16 v[64:67], v[214:217], v[178:181], v[64:67]
	s_waitcnt lgkmcnt(2)
	v_mfma_f32_16x16x32_bf16 v[174:177], v[218:221], v[162:165], v[174:177]
	ds_read_b128 v[162:165], v16
	v_mfma_f32_16x16x32_bf16 v[170:173], v[218:221], v[178:181], v[170:173]
	ds_read_b128 v[178:181], v17
	s_waitcnt lgkmcnt(3)
	s_mov_b32 m0, s43
	v_mfma_f32_16x16x32_bf16 v[72:75], v[158:161], v[222:225], v[72:75]
	global_load_lds_dwordx4 v0, s[68:69]
	v_mfma_f32_16x16x32_bf16 v[76:79], v[166:169], v[222:225], v[76:79]
	v_mfma_f32_16x16x32_bf16 v[80:83], v[214:217], v[222:225], v[80:83]
	v_mfma_f32_16x16x32_bf16 v[32:35], v[218:221], v[222:225], v[32:35]
	ds_read_b128 v[222:225], v18
	s_waitcnt lgkmcnt(3)
	v_mfma_f32_16x16x32_bf16 v[88:91], v[158:161], v[226:229], v[88:91]
	s_mov_b32 m0, s44
	v_mfma_f32_16x16x32_bf16 v[92:95], v[166:169], v[226:229], v[92:95]
	global_load_lds_dwordx4 v2, s[64:65]
	v_mfma_f32_16x16x32_bf16 v[96:99], v[214:217], v[226:229], v[96:99]
	v_mfma_f32_16x16x32_bf16 v[36:39], v[218:221], v[226:229], v[36:39]
	ds_read_b128 v[226:229], v19
	s_waitcnt lgkmcnt(3)
	v_mfma_f32_16x16x32_bf16 v[104:107], v[158:161], v[162:165], v[104:107]
	s_waitcnt lgkmcnt(2)
	v_mfma_f32_16x16x32_bf16 v[116:119], v[158:161], v[178:181], v[116:119]
	s_waitcnt lgkmcnt(1)
	s_mov_b32 m0, s45
	v_mfma_f32_16x16x32_bf16 v[128:131], v[158:161], v[222:225], v[128:131]
	global_load_lds_dwordx4 v2, s[68:69]
	s_waitcnt lgkmcnt(0)
	v_mfma_f32_16x16x32_bf16 v[100:103], v[158:161], v[226:229], v[100:103]
	ds_read_b128 v[158:161], v20
	v_mfma_f32_16x16x32_bf16 v[108:111], v[166:169], v[162:165], v[108:111]
	v_mfma_f32_16x16x32_bf16 v[120:123], v[166:169], v[178:181], v[120:123]
	v_mfma_f32_16x16x32_bf16 v[132:135], v[166:169], v[222:225], v[132:135]
	s_mov_b32 m0, s46
	v_mfma_f32_16x16x32_bf16 v[140:143], v[166:169], v[226:229], v[140:143]
	global_load_lds_dwordx4 v4, s[64:65]
	ds_read_b128 v[166:169], v24
	v_mfma_f32_16x16x32_bf16 v[112:115], v[214:217], v[162:165], v[112:115]
	v_mfma_f32_16x16x32_bf16 v[52:55], v[218:221], v[162:165], v[52:55]
	ds_read_b128 v[162:165], v21
	v_mfma_f32_16x16x32_bf16 v[124:127], v[214:217], v[178:181], v[124:127]
	v_mfma_f32_16x16x32_bf16 v[68:71], v[218:221], v[178:181], v[68:71]
	ds_read_b128 v[178:181], v25
	s_mov_b32 m0, s47
	v_mfma_f32_16x16x32_bf16 v[136:139], v[214:217], v[222:225], v[136:139]
	global_load_lds_dwordx4 v4, s[68:69]
	v_mfma_f32_16x16x32_bf16 v[84:87], v[218:221], v[222:225], v[84:87]
	ds_read_b128 v[222:225], v26
	v_mfma_f32_16x16x32_bf16 v[150:153], v[214:217], v[226:229], v[150:153]
	ds_read_b128 v[214:217], v23
	v_mfma_f32_16x16x32_bf16 v[154:157], v[218:221], v[226:229], v[154:157]
	ds_read_b128 v[218:221], v22
	ds_read_b128 v[226:229], v27
	s_waitcnt lgkmcnt(6)
	v_mfma_f32_16x16x32_bf16 v[40:43], v[158:161], v[166:169], v[40:43]
	s_waitcnt lgkmcnt(5)
	s_mov_b32 m0, s49
	v_mfma_f32_16x16x32_bf16 v[44:47], v[162:165], v[166:169], v[44:47]
	global_load_lds_dwordx4 v146, s[64:65]
	s_waitcnt lgkmcnt(4)
	v_mfma_f32_16x16x32_bf16 v[56:59], v[158:161], v[178:181], v[56:59]
	v_mfma_f32_16x16x32_bf16 v[60:63], v[162:165], v[178:181], v[60:63]
	s_waitcnt lgkmcnt(3)
	v_mfma_f32_16x16x32_bf16 v[72:75], v[158:161], v[222:225], v[72:75]
	v_mfma_f32_16x16x32_bf16 v[76:79], v[162:165], v[222:225], v[76:79]
	s_waitcnt lgkmcnt(2)
	s_mov_b32 m0, s50
	v_mfma_f32_16x16x32_bf16 v[48:51], v[214:217], v[166:169], v[48:51]
	global_load_lds_dwordx4 v146, s[68:69]
	s_waitcnt lgkmcnt(1)
	v_mfma_f32_16x16x32_bf16 v[174:177], v[218:221], v[166:169], v[174:177]
	ds_read_b128 v[166:169], v28
	v_mfma_f32_16x16x32_bf16 v[64:67], v[214:217], v[178:181], v[64:67]
	v_mfma_f32_16x16x32_bf16 v[170:173], v[218:221], v[178:181], v[170:173]
	ds_read_b128 v[178:181], v29
	v_mfma_f32_16x16x32_bf16 v[80:83], v[214:217], v[222:225], v[80:83]
	v_mfma_f32_16x16x32_bf16 v[32:35], v[218:221], v[222:225], v[32:35]
	ds_read_b128 v[222:225], v30
	s_waitcnt lgkmcnt(3)
	v_mfma_f32_16x16x32_bf16 v[88:91], v[158:161], v[226:229], v[88:91]
	v_mfma_f32_16x16x32_bf16 v[92:95], v[162:165], v[226:229], v[92:95]
	v_mfma_f32_16x16x32_bf16 v[96:99], v[214:217], v[226:229], v[96:99]
	v_mfma_f32_16x16x32_bf16 v[36:39], v[218:221], v[226:229], v[36:39]
	ds_read_b128 v[226:229], v31
	s_waitcnt lgkmcnt(3)
	v_mfma_f32_16x16x32_bf16 v[104:107], v[158:161], v[166:169], v[104:107]
	v_mfma_f32_16x16x32_bf16 v[108:111], v[162:165], v[166:169], v[108:111]
	v_mfma_f32_16x16x32_bf16 v[112:115], v[214:217], v[166:169], v[112:115]
	v_mfma_f32_16x16x32_bf16 v[52:55], v[218:221], v[166:169], v[52:55]
	s_waitcnt lgkmcnt(2)
	v_mfma_f32_16x16x32_bf16 v[116:119], v[158:161], v[178:181], v[116:119]
	v_mfma_f32_16x16x32_bf16 v[120:123], v[162:165], v[178:181], v[120:123]
	v_mfma_f32_16x16x32_bf16 v[124:127], v[214:217], v[178:181], v[124:127]
	v_mfma_f32_16x16x32_bf16 v[68:71], v[218:221], v[178:181], v[68:71]
	s_waitcnt lgkmcnt(1)
	v_mfma_f32_16x16x32_bf16 v[128:131], v[158:161], v[222:225], v[128:131]
	v_mfma_f32_16x16x32_bf16 v[132:135], v[162:165], v[222:225], v[132:135]
	v_mfma_f32_16x16x32_bf16 v[136:139], v[214:217], v[222:225], v[136:139]
	v_mfma_f32_16x16x32_bf16 v[84:87], v[218:221], v[222:225], v[84:87]
	s_waitcnt lgkmcnt(0)
	v_mfma_f32_16x16x32_bf16 v[100:103], v[158:161], v[226:229], v[100:103]
	v_mfma_f32_16x16x32_bf16 v[140:143], v[162:165], v[226:229], v[140:143]
	v_mfma_f32_16x16x32_bf16 v[150:153], v[214:217], v[226:229], v[150:153]
	v_mfma_f32_16x16x32_bf16 v[154:157], v[218:221], v[226:229], v[154:157]
	s_add_u32 s64, s0, 0x2e80
	s_addc_u32 s65, s1, 0
	s_add_u32 s68, s14, 0x2e80
	s_waitcnt vmcnt(0)
	s_barrier
	s_addc_u32 s69, s15, 0
	ds_read_b128 v[158:161], v7 offset:32768
	ds_read_b128 v[162:165], v6
	ds_read_b128 v[166:169], v7 offset:34816
	ds_read_b128 v[178:181], v6 offset:2048
	ds_read_b128 v[214:217], v7 offset:36864
	ds_read_b128 v[218:221], v7 offset:38912
	ds_read_b128 v[222:225], v6 offset:4096
	ds_read_b128 v[226:229], v6 offset:6144
	s_waitcnt lgkmcnt(6)
	v_mfma_f32_16x16x32_bf16 v[40:43], v[158:161], v[162:165], v[40:43]
	s_waitcnt lgkmcnt(5)
	v_mfma_f32_16x16x32_bf16 v[44:47], v[166:169], v[162:165], v[44:47]
	s_waitcnt lgkmcnt(4)
	v_mfma_f32_16x16x32_bf16 v[56:59], v[158:161], v[178:181], v[56:59]
	s_mov_b32 m0, s52
	v_mfma_f32_16x16x32_bf16 v[60:63], v[166:169], v[178:181], v[60:63]
	global_load_lds_dwordx4 v0, s[64:65]
	s_waitcnt lgkmcnt(3)
	v_mfma_f32_16x16x32_bf16 v[48:51], v[214:217], v[162:165], v[48:51]
	v_mfma_f32_16x16x32_bf16 v[64:67], v[214:217], v[178:181], v[64:67]
	s_waitcnt lgkmcnt(2)
	v_mfma_f32_16x16x32_bf16 v[174:177], v[218:221], v[162:165], v[174:177]
	ds_read_b128 v[162:165], v6 offset:8192
	v_mfma_f32_16x16x32_bf16 v[170:173], v[218:221], v[178:181], v[170:173]
	ds_read_b128 v[178:181], v6 offset:10240
	s_waitcnt lgkmcnt(3)
	s_mov_b32 m0, s51
	v_mfma_f32_16x16x32_bf16 v[72:75], v[158:161], v[222:225], v[72:75]
	global_load_lds_dwordx4 v0, s[68:69]
	v_mfma_f32_16x16x32_bf16 v[76:79], v[166:169], v[222:225], v[76:79]
	v_mfma_f32_16x16x32_bf16 v[80:83], v[214:217], v[222:225], v[80:83]
	v_mfma_f32_16x16x32_bf16 v[32:35], v[218:221], v[222:225], v[32:35]
	ds_read_b128 v[222:225], v6 offset:12288
	s_waitcnt lgkmcnt(3)
	v_mfma_f32_16x16x32_bf16 v[88:91], v[158:161], v[226:229], v[88:91]
	s_mov_b32 m0, s53
	v_mfma_f32_16x16x32_bf16 v[92:95], v[166:169], v[226:229], v[92:95]
	global_load_lds_dwordx4 v2, s[64:65]
	v_mfma_f32_16x16x32_bf16 v[96:99], v[214:217], v[226:229], v[96:99]
	v_mfma_f32_16x16x32_bf16 v[36:39], v[218:221], v[226:229], v[36:39]
	ds_read_b128 v[226:229], v6 offset:14336
	s_waitcnt lgkmcnt(3)
	v_mfma_f32_16x16x32_bf16 v[104:107], v[158:161], v[162:165], v[104:107]
	s_waitcnt lgkmcnt(2)
	v_mfma_f32_16x16x32_bf16 v[116:119], v[158:161], v[178:181], v[116:119]
	s_waitcnt lgkmcnt(1)
	s_mov_b32 m0, s54
	v_mfma_f32_16x16x32_bf16 v[128:131], v[158:161], v[222:225], v[128:131]
	global_load_lds_dwordx4 v2, s[68:69]
	s_waitcnt lgkmcnt(0)
	v_mfma_f32_16x16x32_bf16 v[100:103], v[158:161], v[226:229], v[100:103]
	ds_read_b128 v[158:161], v7 offset:33792
	v_mfma_f32_16x16x32_bf16 v[108:111], v[166:169], v[162:165], v[108:111]
	v_mfma_f32_16x16x32_bf16 v[120:123], v[166:169], v[178:181], v[120:123]
	v_mfma_f32_16x16x32_bf16 v[132:135], v[166:169], v[222:225], v[132:135]
	s_mov_b32 m0, s55
	v_mfma_f32_16x16x32_bf16 v[140:143], v[166:169], v[226:229], v[140:143]
	global_load_lds_dwordx4 v4, s[64:65]
	ds_read_b128 v[166:169], v6 offset:1024
	v_mfma_f32_16x16x32_bf16 v[112:115], v[214:217], v[162:165], v[112:115]
	v_mfma_f32_16x16x32_bf16 v[52:55], v[218:221], v[162:165], v[52:55]
	ds_read_b128 v[162:165], v7 offset:35840
	v_mfma_f32_16x16x32_bf16 v[124:127], v[214:217], v[178:181], v[124:127]
	v_mfma_f32_16x16x32_bf16 v[68:71], v[218:221], v[178:181], v[68:71]
	ds_read_b128 v[178:181], v6 offset:3072
	s_mov_b32 m0, s58
	v_mfma_f32_16x16x32_bf16 v[136:139], v[214:217], v[222:225], v[136:139]
	global_load_lds_dwordx4 v4, s[68:69]
	v_mfma_f32_16x16x32_bf16 v[84:87], v[218:221], v[222:225], v[84:87]
	ds_read_b128 v[222:225], v6 offset:5120
	v_mfma_f32_16x16x32_bf16 v[150:153], v[214:217], v[226:229], v[150:153]
	ds_read_b128 v[214:217], v7 offset:37888
	v_mfma_f32_16x16x32_bf16 v[154:157], v[218:221], v[226:229], v[154:157]
	ds_read_b128 v[218:221], v7 offset:39936
	ds_read_b128 v[226:229], v6 offset:7168
	s_waitcnt lgkmcnt(6)
	v_mfma_f32_16x16x32_bf16 v[40:43], v[158:161], v[166:169], v[40:43]
	s_waitcnt lgkmcnt(5)
	s_mov_b32 m0, s62
	v_mfma_f32_16x16x32_bf16 v[44:47], v[162:165], v[166:169], v[44:47]
	global_load_lds_dwordx4 v146, s[64:65]
	s_waitcnt lgkmcnt(4)
	v_mfma_f32_16x16x32_bf16 v[56:59], v[158:161], v[178:181], v[56:59]
	v_mfma_f32_16x16x32_bf16 v[60:63], v[162:165], v[178:181], v[60:63]
	s_waitcnt lgkmcnt(3)
	v_mfma_f32_16x16x32_bf16 v[72:75], v[158:161], v[222:225], v[72:75]
	v_mfma_f32_16x16x32_bf16 v[76:79], v[162:165], v[222:225], v[76:79]
	s_waitcnt lgkmcnt(2)
	s_mov_b32 m0, s63
	v_mfma_f32_16x16x32_bf16 v[48:51], v[214:217], v[166:169], v[48:51]
	global_load_lds_dwordx4 v146, s[68:69]
	s_waitcnt lgkmcnt(1)
	v_mfma_f32_16x16x32_bf16 v[174:177], v[218:221], v[166:169], v[174:177]
	ds_read_b128 v[166:169], v6 offset:9216
	v_mfma_f32_16x16x32_bf16 v[64:67], v[214:217], v[178:181], v[64:67]
	v_mfma_f32_16x16x32_bf16 v[170:173], v[218:221], v[178:181], v[170:173]
	ds_read_b128 v[178:181], v6 offset:11264
	v_mfma_f32_16x16x32_bf16 v[80:83], v[214:217], v[222:225], v[80:83]
	v_mfma_f32_16x16x32_bf16 v[32:35], v[218:221], v[222:225], v[32:35]
	ds_read_b128 v[222:225], v6 offset:13312
	s_waitcnt lgkmcnt(3)
	v_mfma_f32_16x16x32_bf16 v[88:91], v[158:161], v[226:229], v[88:91]
	v_mfma_f32_16x16x32_bf16 v[92:95], v[162:165], v[226:229], v[92:95]
	v_mfma_f32_16x16x32_bf16 v[96:99], v[214:217], v[226:229], v[96:99]
	v_mfma_f32_16x16x32_bf16 v[36:39], v[218:221], v[226:229], v[36:39]
	ds_read_b128 v[226:229], v6 offset:15360
	s_waitcnt lgkmcnt(3)
	v_mfma_f32_16x16x32_bf16 v[104:107], v[158:161], v[166:169], v[104:107]
	v_mfma_f32_16x16x32_bf16 v[108:111], v[162:165], v[166:169], v[108:111]
	v_mfma_f32_16x16x32_bf16 v[112:115], v[214:217], v[166:169], v[112:115]
	v_mfma_f32_16x16x32_bf16 v[52:55], v[218:221], v[166:169], v[52:55]
	s_waitcnt lgkmcnt(2)
	v_mfma_f32_16x16x32_bf16 v[116:119], v[158:161], v[178:181], v[116:119]
	v_mfma_f32_16x16x32_bf16 v[120:123], v[162:165], v[178:181], v[120:123]
	v_mfma_f32_16x16x32_bf16 v[124:127], v[214:217], v[178:181], v[124:127]
	v_mfma_f32_16x16x32_bf16 v[68:71], v[218:221], v[178:181], v[68:71]
	s_waitcnt lgkmcnt(1)
	v_mfma_f32_16x16x32_bf16 v[128:131], v[158:161], v[222:225], v[128:131]
	v_mfma_f32_16x16x32_bf16 v[132:135], v[162:165], v[222:225], v[132:135]
	v_mfma_f32_16x16x32_bf16 v[136:139], v[214:217], v[222:225], v[136:139]
	v_mfma_f32_16x16x32_bf16 v[84:87], v[218:221], v[222:225], v[84:87]
	s_waitcnt lgkmcnt(0)
	v_mfma_f32_16x16x32_bf16 v[100:103], v[158:161], v[226:229], v[100:103]
	v_mfma_f32_16x16x32_bf16 v[140:143], v[162:165], v[226:229], v[140:143]
	v_mfma_f32_16x16x32_bf16 v[150:153], v[214:217], v[226:229], v[150:153]
	v_mfma_f32_16x16x32_bf16 v[154:157], v[218:221], v[226:229], v[154:157]
	s_add_u32 s64, s0, 0x2f00
	s_addc_u32 s65, s1, 0
	s_add_u32 s68, s14, 0x2f00
	s_waitcnt vmcnt(0)
	s_barrier
	s_addc_u32 s69, s15, 0
	v_lshl_add_u64 v[158:159], s[64:65], 0, v[0:1]
	s_mov_b32 s70, m0
	s_mov_b32 m0, s42
	s_nop 0
	global_load_lds_dwordx4 v[158:159], off
	s_mov_b32 m0, s70
	v_lshl_add_u64 v[158:159], s[68:69], 0, v[0:1]
	s_mov_b32 s70, m0
	s_mov_b32 m0, s43
	s_nop 0
	global_load_lds_dwordx4 v[158:159], off
	s_mov_b32 m0, s70
	v_lshl_add_u64 v[158:159], s[64:65], 0, v[2:3]
	s_mov_b32 s70, m0
	s_mov_b32 m0, s44
	s_nop 0
	global_load_lds_dwordx4 v[158:159], off
	s_mov_b32 m0, s70
	v_lshl_add_u64 v[158:159], s[68:69], 0, v[2:3]
	s_mov_b32 s70, m0
	s_mov_b32 m0, s45
	s_nop 0
	global_load_lds_dwordx4 v[158:159], off
	s_mov_b32 m0, s70
	v_lshl_add_u64 v[158:159], s[64:65], 0, v[4:5]
	s_mov_b32 s70, m0
	s_mov_b32 m0, s46
	s_nop 0
	global_load_lds_dwordx4 v[158:159], off
	s_mov_b32 m0, s70
	v_lshl_add_u64 v[158:159], s[68:69], 0, v[4:5]
	s_mov_b32 s70, m0
	s_mov_b32 m0, s47
	s_nop 0
	global_load_lds_dwordx4 v[158:159], off
	s_mov_b32 m0, s70
	v_lshl_add_u64 v[158:159], s[64:65], 0, v[146:147]
	s_mov_b32 s64, m0
	s_mov_b32 m0, s49
	s_nop 0
	global_load_lds_dwordx4 v[158:159], off
	s_mov_b32 m0, s64
	v_lshl_add_u64 v[158:159], s[68:69], 0, v[146:147]
	s_mov_b32 s64, m0
	s_mov_b32 m0, s50
	s_nop 0
	global_load_lds_dwordx4 v[158:159], off
	s_mov_b32 m0, s64
	ds_read_b128 v[158:161], v8
	ds_read_b128 v[162:165], v9
	ds_read_b128 v[166:169], v11
	ds_read_b128 v[214:217], v10
	ds_read_b128 v[178:181], v12
	ds_read_b128 v[218:221], v13
	ds_read_b128 v[222:225], v14
	ds_read_b128 v[226:229], v15
	s_waitcnt lgkmcnt(3)
	v_mfma_f32_16x16x32_bf16 v[40:43], v[158:161], v[178:181], v[40:43]
	v_mfma_f32_16x16x32_bf16 v[44:47], v[162:165], v[178:181], v[44:47]
	v_mfma_f32_16x16x32_bf16 v[48:51], v[166:169], v[178:181], v[48:51]
	v_mfma_f32_16x16x32_bf16 v[174:177], v[214:217], v[178:181], v[174:177]
	ds_read_b128 v[178:181], v16
	s_waitcnt lgkmcnt(3)
	v_mfma_f32_16x16x32_bf16 v[56:59], v[158:161], v[218:221], v[56:59]
	v_mfma_f32_16x16x32_bf16 v[60:63], v[162:165], v[218:221], v[60:63]
	v_mfma_f32_16x16x32_bf16 v[64:67], v[166:169], v[218:221], v[64:67]
	v_mfma_f32_16x16x32_bf16 v[170:173], v[214:217], v[218:221], v[170:173]
	ds_read_b128 v[218:221], v17
	s_waitcnt lgkmcnt(3)
	v_mfma_f32_16x16x32_bf16 v[72:75], v[158:161], v[222:225], v[72:75]
	v_mfma_f32_16x16x32_bf16 v[76:79], v[162:165], v[222:225], v[76:79]
	v_mfma_f32_16x16x32_bf16 v[80:83], v[166:169], v[222:225], v[80:83]
	v_mfma_f32_16x16x32_bf16 v[32:35], v[214:217], v[222:225], v[32:35]
	ds_read_b128 v[222:225], v18
	s_waitcnt lgkmcnt(3)
	v_mfma_f32_16x16x32_bf16 v[88:91], v[158:161], v[226:229], v[88:91]
	v_mfma_f32_16x16x32_bf16 v[92:95], v[162:165], v[226:229], v[92:95]
	v_mfma_f32_16x16x32_bf16 v[96:99], v[166:169], v[226:229], v[96:99]
	v_mfma_f32_16x16x32_bf16 v[36:39], v[214:217], v[226:229], v[36:39]
	ds_read_b128 v[226:229], v19
	s_waitcnt lgkmcnt(3)
	v_mfma_f32_16x16x32_bf16 v[104:107], v[158:161], v[178:181], v[104:107]
	v_mfma_f32_16x16x32_bf16 v[108:111], v[162:165], v[178:181], v[108:111]
	v_mfma_f32_16x16x32_bf16 v[112:115], v[166:169], v[178:181], v[112:115]
	v_mfma_f32_16x16x32_bf16 v[52:55], v[214:217], v[178:181], v[52:55]
	s_waitcnt lgkmcnt(2)
	v_mfma_f32_16x16x32_bf16 v[116:119], v[158:161], v[218:221], v[116:119]
	v_mfma_f32_16x16x32_bf16 v[120:123], v[162:165], v[218:221], v[120:123]
	v_mfma_f32_16x16x32_bf16 v[124:127], v[166:169], v[218:221], v[124:127]
	v_mfma_f32_16x16x32_bf16 v[68:71], v[214:217], v[218:221], v[68:71]
	s_waitcnt lgkmcnt(1)
	v_mfma_f32_16x16x32_bf16 v[132:135], v[162:165], v[222:225], v[132:135]
	v_mfma_f32_16x16x32_bf16 v[84:87], v[214:217], v[222:225], v[84:87]
	s_waitcnt lgkmcnt(0)
	v_mfma_f32_16x16x32_bf16 v[100:103], v[158:161], v[226:229], v[100:103]
	v_mfma_f32_16x16x32_bf16 v[150:153], v[166:169], v[226:229], v[150:153]
	v_mfma_f32_16x16x32_bf16 v[154:157], v[214:217], v[226:229], v[154:157]
	v_mfma_f32_16x16x32_bf16 v[128:131], v[158:161], v[222:225], v[128:131]
	v_mfma_f32_16x16x32_bf16 v[136:139], v[166:169], v[222:225], v[136:139]
	v_mfma_f32_16x16x32_bf16 v[140:143], v[162:165], v[226:229], v[140:143]
	ds_read_b128 v[158:161], v20
	ds_read_b128 v[162:165], v21
	ds_read_b128 v[166:169], v23
	ds_read_b128 v[214:217], v22
	ds_read_b128 v[178:181], v24
	ds_read_b128 v[218:221], v25
	ds_read_b128 v[222:225], v26
	ds_read_b128 v[226:229], v27
	s_waitcnt lgkmcnt(3)
	v_mfma_f32_16x16x32_bf16 v[40:43], v[158:161], v[178:181], v[40:43]
	v_mfma_f32_16x16x32_bf16 v[44:47], v[162:165], v[178:181], v[44:47]
	v_mfma_f32_16x16x32_bf16 v[48:51], v[166:169], v[178:181], v[48:51]
	v_mfma_f32_16x16x32_bf16 v[174:177], v[214:217], v[178:181], v[174:177]
	ds_read_b128 v[178:181], v28
	s_waitcnt lgkmcnt(3)
	v_mfma_f32_16x16x32_bf16 v[56:59], v[158:161], v[218:221], v[56:59]
	v_mfma_f32_16x16x32_bf16 v[60:63], v[162:165], v[218:221], v[60:63]
	v_mfma_f32_16x16x32_bf16 v[64:67], v[166:169], v[218:221], v[64:67]
	v_mfma_f32_16x16x32_bf16 v[170:173], v[214:217], v[218:221], v[170:173]
	ds_read_b128 v[218:221], v29
	s_waitcnt lgkmcnt(3)
	v_mfma_f32_16x16x32_bf16 v[72:75], v[158:161], v[222:225], v[72:75]
	v_mfma_f32_16x16x32_bf16 v[76:79], v[162:165], v[222:225], v[76:79]
	v_mfma_f32_16x16x32_bf16 v[80:83], v[166:169], v[222:225], v[80:83]
	v_mfma_f32_16x16x32_bf16 v[32:35], v[214:217], v[222:225], v[32:35]
	ds_read_b128 v[222:225], v30
	s_waitcnt lgkmcnt(3)
	v_mfma_f32_16x16x32_bf16 v[88:91], v[158:161], v[226:229], v[88:91]
	v_mfma_f32_16x16x32_bf16 v[92:95], v[162:165], v[226:229], v[92:95]
	v_mfma_f32_16x16x32_bf16 v[96:99], v[166:169], v[226:229], v[96:99]
	v_mfma_f32_16x16x32_bf16 v[36:39], v[214:217], v[226:229], v[36:39]
	ds_read_b128 v[226:229], v31
	s_waitcnt lgkmcnt(3)
	v_mfma_f32_16x16x32_bf16 v[104:107], v[158:161], v[178:181], v[104:107]
	v_mfma_f32_16x16x32_bf16 v[108:111], v[162:165], v[178:181], v[108:111]
	v_mfma_f32_16x16x32_bf16 v[112:115], v[166:169], v[178:181], v[112:115]
	v_mfma_f32_16x16x32_bf16 v[52:55], v[214:217], v[178:181], v[52:55]
	s_waitcnt lgkmcnt(2)
	v_mfma_f32_16x16x32_bf16 v[116:119], v[158:161], v[218:221], v[116:119]
	v_mfma_f32_16x16x32_bf16 v[120:123], v[162:165], v[218:221], v[120:123]
	v_mfma_f32_16x16x32_bf16 v[124:127], v[166:169], v[218:221], v[124:127]
	v_mfma_f32_16x16x32_bf16 v[68:71], v[214:217], v[218:221], v[68:71]
	s_waitcnt lgkmcnt(1)
	v_mfma_f32_16x16x32_bf16 v[132:135], v[162:165], v[222:225], v[132:135]
	v_mfma_f32_16x16x32_bf16 v[84:87], v[214:217], v[222:225], v[84:87]
	s_waitcnt lgkmcnt(0)
	v_mfma_f32_16x16x32_bf16 v[100:103], v[158:161], v[226:229], v[100:103]
	v_mfma_f32_16x16x32_bf16 v[150:153], v[166:169], v[226:229], v[150:153]
	v_mfma_f32_16x16x32_bf16 v[154:157], v[214:217], v[226:229], v[154:157]
	v_mfma_f32_16x16x32_bf16 v[128:131], v[158:161], v[222:225], v[128:131]
	v_mfma_f32_16x16x32_bf16 v[136:139], v[166:169], v[222:225], v[136:139]
	v_mfma_f32_16x16x32_bf16 v[140:143], v[162:165], v[226:229], v[140:143]
	s_add_u32 s0, s0, 0x2f80
	s_addc_u32 s1, s1, 0
	s_add_u32 s14, s14, 0x2f80
	s_waitcnt vmcnt(0)
	s_barrier
	s_addc_u32 s15, s15, 0
	v_lshl_add_u64 v[158:159], s[0:1], 0, v[0:1]
	s_mov_b32 s64, m0
	s_mov_b32 m0, s52
	s_nop 0
	global_load_lds_dwordx4 v[158:159], off
	s_mov_b32 m0, s64
	v_lshl_add_u64 v[158:159], s[14:15], 0, v[0:1]
	s_mov_b32 s52, m0
	s_mov_b32 m0, s51
	s_nop 0
	global_load_lds_dwordx4 v[158:159], off
	s_mov_b32 m0, s52
	v_lshl_add_u64 v[158:159], s[0:1], 0, v[2:3]
	s_mov_b32 s51, m0
	s_mov_b32 m0, s53
	s_nop 0
	global_load_lds_dwordx4 v[158:159], off
	s_mov_b32 m0, s51
	v_lshl_add_u64 v[158:159], s[14:15], 0, v[2:3]
	s_mov_b32 s51, m0
	s_mov_b32 m0, s54
	s_nop 0
	global_load_lds_dwordx4 v[158:159], off
	s_mov_b32 m0, s51
	v_lshl_add_u64 v[158:159], s[0:1], 0, v[4:5]
	s_mov_b32 s51, m0
	s_mov_b32 m0, s55
	s_nop 0
	global_load_lds_dwordx4 v[158:159], off
	s_mov_b32 m0, s51
	v_lshl_add_u64 v[158:159], s[14:15], 0, v[4:5]
	s_mov_b32 s51, m0
	s_mov_b32 m0, s58
	s_nop 0
	global_load_lds_dwordx4 v[158:159], off
	s_mov_b32 m0, s51
	v_lshl_add_u64 v[158:159], s[0:1], 0, v[146:147]
	s_mov_b32 s0, m0
	s_mov_b32 m0, s62
	s_nop 0
	global_load_lds_dwordx4 v[158:159], off
	s_mov_b32 m0, s0
	v_lshl_add_u64 v[158:159], s[14:15], 0, v[146:147]
	s_mov_b32 s0, m0
	s_mov_b32 m0, s63
	s_nop 0
	global_load_lds_dwordx4 v[158:159], off
	s_mov_b32 m0, s0
	ds_read_b128 v[158:161], v7 offset:32768
	ds_read_b128 v[162:165], v7 offset:34816
	ds_read_b128 v[166:169], v7 offset:36864
	ds_read_b128 v[214:217], v7 offset:38912
	ds_read_b128 v[178:181], v6
	ds_read_b128 v[218:221], v6 offset:2048
	ds_read_b128 v[222:225], v6 offset:4096
	ds_read_b128 v[226:229], v6 offset:6144
	s_waitcnt lgkmcnt(3)
	v_mfma_f32_16x16x32_bf16 v[40:43], v[158:161], v[178:181], v[40:43]
	v_mfma_f32_16x16x32_bf16 v[44:47], v[162:165], v[178:181], v[44:47]
	v_mfma_f32_16x16x32_bf16 v[48:51], v[166:169], v[178:181], v[48:51]
	v_mfma_f32_16x16x32_bf16 v[174:177], v[214:217], v[178:181], v[174:177]
	ds_read_b128 v[178:181], v6 offset:8192
	s_waitcnt lgkmcnt(3)
	v_mfma_f32_16x16x32_bf16 v[56:59], v[158:161], v[218:221], v[56:59]
	v_mfma_f32_16x16x32_bf16 v[60:63], v[162:165], v[218:221], v[60:63]
	v_mfma_f32_16x16x32_bf16 v[64:67], v[166:169], v[218:221], v[64:67]
	v_mfma_f32_16x16x32_bf16 v[170:173], v[214:217], v[218:221], v[170:173]
	ds_read_b128 v[218:221], v6 offset:10240
	s_waitcnt lgkmcnt(3)
	v_mfma_f32_16x16x32_bf16 v[72:75], v[158:161], v[222:225], v[72:75]
	v_mfma_f32_16x16x32_bf16 v[76:79], v[162:165], v[222:225], v[76:79]
	v_mfma_f32_16x16x32_bf16 v[80:83], v[166:169], v[222:225], v[80:83]
	v_mfma_f32_16x16x32_bf16 v[32:35], v[214:217], v[222:225], v[32:35]
	ds_read_b128 v[222:225], v6 offset:12288
	s_waitcnt lgkmcnt(3)
	v_mfma_f32_16x16x32_bf16 v[88:91], v[158:161], v[226:229], v[88:91]
	v_mfma_f32_16x16x32_bf16 v[92:95], v[162:165], v[226:229], v[92:95]
	v_mfma_f32_16x16x32_bf16 v[96:99], v[166:169], v[226:229], v[96:99]
	v_mfma_f32_16x16x32_bf16 v[36:39], v[214:217], v[226:229], v[36:39]
	ds_read_b128 v[226:229], v6 offset:14336
	s_waitcnt lgkmcnt(3)
	v_mfma_f32_16x16x32_bf16 v[104:107], v[158:161], v[178:181], v[104:107]
	v_mfma_f32_16x16x32_bf16 v[108:111], v[162:165], v[178:181], v[108:111]
	v_mfma_f32_16x16x32_bf16 v[112:115], v[166:169], v[178:181], v[112:115]
	v_mfma_f32_16x16x32_bf16 v[52:55], v[214:217], v[178:181], v[52:55]
	s_waitcnt lgkmcnt(2)
	v_mfma_f32_16x16x32_bf16 v[116:119], v[158:161], v[218:221], v[116:119]
	v_mfma_f32_16x16x32_bf16 v[120:123], v[162:165], v[218:221], v[120:123]
	v_mfma_f32_16x16x32_bf16 v[124:127], v[166:169], v[218:221], v[124:127]
	v_mfma_f32_16x16x32_bf16 v[68:71], v[214:217], v[218:221], v[68:71]
	s_waitcnt lgkmcnt(1)
	v_mfma_f32_16x16x32_bf16 v[132:135], v[162:165], v[222:225], v[132:135]
	v_mfma_f32_16x16x32_bf16 v[84:87], v[214:217], v[222:225], v[84:87]
	s_waitcnt lgkmcnt(0)
	v_mfma_f32_16x16x32_bf16 v[100:103], v[158:161], v[226:229], v[100:103]
	v_mfma_f32_16x16x32_bf16 v[150:153], v[166:169], v[226:229], v[150:153]
	v_mfma_f32_16x16x32_bf16 v[154:157], v[214:217], v[226:229], v[154:157]
	v_mfma_f32_16x16x32_bf16 v[128:131], v[158:161], v[222:225], v[128:131]
	v_mfma_f32_16x16x32_bf16 v[136:139], v[166:169], v[222:225], v[136:139]
	v_mfma_f32_16x16x32_bf16 v[140:143], v[162:165], v[226:229], v[140:143]
	ds_read_b128 v[158:161], v7 offset:33792
	ds_read_b128 v[162:165], v7 offset:35840
	ds_read_b128 v[166:169], v7 offset:37888
	ds_read_b128 v[214:217], v7 offset:39936
	ds_read_b128 v[178:181], v6 offset:1024
	ds_read_b128 v[218:221], v6 offset:3072
	ds_read_b128 v[222:225], v6 offset:5120
	ds_read_b128 v[226:229], v6 offset:7168
	s_waitcnt lgkmcnt(3)
	v_mfma_f32_16x16x32_bf16 v[40:43], v[158:161], v[178:181], v[40:43]
	v_mfma_f32_16x16x32_bf16 v[44:47], v[162:165], v[178:181], v[44:47]
	v_mfma_f32_16x16x32_bf16 v[48:51], v[166:169], v[178:181], v[48:51]
	v_mfma_f32_16x16x32_bf16 v[174:177], v[214:217], v[178:181], v[174:177]
	ds_read_b128 v[178:181], v6 offset:9216
	s_waitcnt lgkmcnt(3)
	v_mfma_f32_16x16x32_bf16 v[56:59], v[158:161], v[218:221], v[56:59]
	v_mfma_f32_16x16x32_bf16 v[60:63], v[162:165], v[218:221], v[60:63]
	v_mfma_f32_16x16x32_bf16 v[64:67], v[166:169], v[218:221], v[64:67]
	v_mfma_f32_16x16x32_bf16 v[170:173], v[214:217], v[218:221], v[170:173]
	ds_read_b128 v[218:221], v6 offset:11264
	s_waitcnt lgkmcnt(3)
	v_mfma_f32_16x16x32_bf16 v[72:75], v[158:161], v[222:225], v[72:75]
	v_mfma_f32_16x16x32_bf16 v[76:79], v[162:165], v[222:225], v[76:79]
	v_mfma_f32_16x16x32_bf16 v[80:83], v[166:169], v[222:225], v[80:83]
	v_mfma_f32_16x16x32_bf16 v[32:35], v[214:217], v[222:225], v[32:35]
	ds_read_b128 v[222:225], v6 offset:13312
	s_waitcnt lgkmcnt(3)
	v_mfma_f32_16x16x32_bf16 v[88:91], v[158:161], v[226:229], v[88:91]
	v_mfma_f32_16x16x32_bf16 v[92:95], v[162:165], v[226:229], v[92:95]
	v_mfma_f32_16x16x32_bf16 v[96:99], v[166:169], v[226:229], v[96:99]
	v_mfma_f32_16x16x32_bf16 v[36:39], v[214:217], v[226:229], v[36:39]
	ds_read_b128 v[226:229], v6 offset:15360
	s_waitcnt lgkmcnt(3)
	v_mfma_f32_16x16x32_bf16 v[104:107], v[158:161], v[178:181], v[104:107]
	v_mfma_f32_16x16x32_bf16 v[108:111], v[162:165], v[178:181], v[108:111]
	v_mfma_f32_16x16x32_bf16 v[112:115], v[166:169], v[178:181], v[112:115]
	v_mfma_f32_16x16x32_bf16 v[52:55], v[214:217], v[178:181], v[52:55]
	s_waitcnt lgkmcnt(2)
	v_mfma_f32_16x16x32_bf16 v[116:119], v[158:161], v[218:221], v[116:119]
	v_mfma_f32_16x16x32_bf16 v[120:123], v[162:165], v[218:221], v[120:123]
	v_mfma_f32_16x16x32_bf16 v[124:127], v[166:169], v[218:221], v[124:127]
	v_mfma_f32_16x16x32_bf16 v[68:71], v[214:217], v[218:221], v[68:71]
	s_waitcnt lgkmcnt(1)
	v_mfma_f32_16x16x32_bf16 v[132:135], v[162:165], v[222:225], v[132:135]
	v_mfma_f32_16x16x32_bf16 v[84:87], v[214:217], v[222:225], v[84:87]
	s_waitcnt lgkmcnt(0)
	v_mfma_f32_16x16x32_bf16 v[100:103], v[158:161], v[226:229], v[100:103]
	v_mfma_f32_16x16x32_bf16 v[150:153], v[166:169], v[226:229], v[150:153]
	v_mfma_f32_16x16x32_bf16 v[154:157], v[214:217], v[226:229], v[154:157]
	v_mfma_f32_16x16x32_bf16 v[128:131], v[158:161], v[222:225], v[128:131]
	v_mfma_f32_16x16x32_bf16 v[136:139], v[166:169], v[222:225], v[136:139]
	v_mfma_f32_16x16x32_bf16 v[140:143], v[162:165], v[226:229], v[140:143]
	s_waitcnt vmcnt(0)
	s_barrier
	v_lshl_add_u64 v[6:7], s[20:21], 0, v[0:1]
	s_mov_b32 s0, m0
	s_mov_b32 m0, s42
	s_nop 0
	global_load_lds_dwordx4 v[6:7], off
	s_mov_b32 m0, s0
	v_lshl_add_u64 v[0:1], s[22:23], 0, v[0:1]
	s_mov_b32 s0, m0
	s_mov_b32 m0, s43
	s_nop 0
	global_load_lds_dwordx4 v[0:1], off
	s_mov_b32 m0, s0
	v_lshl_add_u64 v[0:1], s[20:21], 0, v[2:3]
	s_mov_b32 s0, m0
	s_mov_b32 m0, s44
	s_nop 0
	global_load_lds_dwordx4 v[0:1], off
	s_mov_b32 m0, s0
	v_lshl_add_u64 v[0:1], s[22:23], 0, v[2:3]
	s_mov_b32 s0, m0
	s_mov_b32 m0, s45
	s_nop 0
	global_load_lds_dwordx4 v[0:1], off
	s_mov_b32 m0, s0
	v_lshl_add_u64 v[0:1], s[20:21], 0, v[4:5]
	s_mov_b32 s0, m0
	s_mov_b32 m0, s46
	s_nop 0
	global_load_lds_dwordx4 v[0:1], off
	s_mov_b32 m0, s0
	v_lshl_add_u64 v[0:1], s[22:23], 0, v[4:5]
	s_mov_b32 s0, m0
	s_mov_b32 m0, s47
	s_nop 0
	global_load_lds_dwordx4 v[0:1], off
	s_mov_b32 m0, s0
	v_lshl_add_u64 v[0:1], s[20:21], 0, v[146:147]
	s_mov_b32 s0, m0
	s_mov_b32 m0, s49
	s_nop 0
	global_load_lds_dwordx4 v[0:1], off
	s_mov_b32 m0, s0
	v_lshl_add_u64 v[0:1], s[22:23], 0, v[146:147]
	s_mov_b32 s0, m0
	s_mov_b32 m0, s50
	s_nop 0
	global_load_lds_dwordx4 v[0:1], off
	s_mov_b32 m0, s0
	ds_read_b128 v[0:3], v8
	ds_read_b128 v[4:7], v9
	ds_read_b128 v[158:161], v11
	ds_read_b128 v[8:11], v10
	ds_read_b128 v[162:165], v12
	ds_read_b128 v[166:169], v13
	ds_read_b128 v[178:181], v14
	ds_read_b128 v[12:15], v15
	s_waitcnt lgkmcnt(3)
	v_mfma_f32_16x16x32_bf16 v[40:43], v[0:3], v[162:165], v[40:43]
	v_mfma_f32_16x16x32_bf16 v[44:47], v[4:7], v[162:165], v[44:47]
	v_mfma_f32_16x16x32_bf16 v[48:51], v[158:161], v[162:165], v[48:51]
	v_mfma_f32_16x16x32_bf16 v[162:165], v[8:11], v[162:165], v[174:177]
	s_nop 2
	ds_read_b128 v[174:177], v16
	s_waitcnt lgkmcnt(3)
	v_mfma_f32_16x16x32_bf16 v[56:59], v[0:3], v[166:169], v[56:59]
	v_mfma_f32_16x16x32_bf16 v[60:63], v[4:7], v[166:169], v[60:63]
	v_mfma_f32_16x16x32_bf16 v[64:67], v[158:161], v[166:169], v[64:67]
	v_mfma_f32_16x16x32_bf16 v[166:169], v[8:11], v[166:169], v[170:173]
	s_nop 2
	ds_read_b128 v[170:173], v17
	s_waitcnt lgkmcnt(3)
	v_mfma_f32_16x16x32_bf16 v[72:75], v[0:3], v[178:181], v[72:75]
	v_mfma_f32_16x16x32_bf16 v[76:79], v[4:7], v[178:181], v[76:79]
	v_mfma_f32_16x16x32_bf16 v[80:83], v[158:161], v[178:181], v[80:83]
	v_mfma_f32_16x16x32_bf16 v[32:35], v[8:11], v[178:181], v[32:35]
	ds_read_b128 v[178:181], v18
	s_waitcnt lgkmcnt(3)
	v_mfma_f32_16x16x32_bf16 v[214:217], v[0:3], v[12:15], v[88:91]
	v_mfma_f32_16x16x32_bf16 v[218:221], v[4:7], v[12:15], v[92:95]
	v_mfma_f32_16x16x32_bf16 v[222:225], v[158:161], v[12:15], v[96:99]
	v_mfma_f32_16x16x32_bf16 v[12:15], v[8:11], v[12:15], v[36:39]
	ds_read_b128 v[16:19], v19
	s_waitcnt lgkmcnt(3)
	v_mfma_f32_16x16x32_bf16 v[36:39], v[0:3], v[174:177], v[104:107]
	v_mfma_f32_16x16x32_bf16 v[226:229], v[4:7], v[174:177], v[108:111]
	v_mfma_f32_16x16x32_bf16 v[112:115], v[158:161], v[174:177], v[112:115]
	s_waitcnt lgkmcnt(2)
	v_mfma_f32_16x16x32_bf16 v[116:119], v[0:3], v[170:173], v[116:119]
	v_mfma_f32_16x16x32_bf16 v[120:123], v[4:7], v[170:173], v[120:123]
	v_mfma_f32_16x16x32_bf16 v[124:127], v[158:161], v[170:173], v[124:127]
	s_waitcnt lgkmcnt(1)
	v_mfma_f32_16x16x32_bf16 v[128:131], v[0:3], v[178:181], v[128:131]
	v_mfma_f32_16x16x32_bf16 v[132:135], v[4:7], v[178:181], v[132:135]
	s_waitcnt lgkmcnt(0)
	v_mfma_f32_16x16x32_bf16 v[0:3], v[0:3], v[16:19], v[100:103]
	v_mfma_f32_16x16x32_bf16 v[4:7], v[4:7], v[16:19], v[140:143]
	v_mfma_f32_16x16x32_bf16 v[140:143], v[158:161], v[16:19], v[150:153]
	v_mfma_f32_16x16x32_bf16 v[150:153], v[8:11], v[16:19], v[154:157]
	v_mfma_f32_16x16x32_bf16 v[174:177], v[8:11], v[174:177], v[52:55]
	v_mfma_f32_16x16x32_bf16 v[170:173], v[8:11], v[170:173], v[68:71]
	v_mfma_f32_16x16x32_bf16 v[136:139], v[158:161], v[178:181], v[136:139]
	v_mfma_f32_16x16x32_bf16 v[178:181], v[8:11], v[178:181], v[84:87]
	ds_read_b128 v[8:11], v20
	ds_read_b128 v[154:157], v21
	ds_read_b128 v[158:161], v23
	ds_read_b128 v[230:233], v22
	ds_read_b128 v[16:19], v24
	ds_read_b128 v[20:23], v25
	ds_read_b128 v[52:55], v26
	ds_read_b128 v[24:27], v27
	s_waitcnt lgkmcnt(3)
	v_mfma_f32_16x16x32_bf16 v[234:237], v[8:11], v[16:19], v[40:43]
	v_mfma_f32_16x16x32_bf16 v[238:241], v[154:157], v[16:19], v[44:47]
	v_mfma_f32_16x16x32_bf16 v[242:245], v[158:161], v[16:19], v[48:51]
	v_mfma_f32_16x16x32_bf16 v[162:165], v[230:233], v[16:19], v[162:165]
	ds_read_b128 v[16:19], v28
	s_waitcnt lgkmcnt(3)
	v_mfma_f32_16x16x32_bf16 v[108:111], v[8:11], v[20:23], v[56:59]
	v_mfma_f32_16x16x32_bf16 v[104:107], v[154:157], v[20:23], v[60:63]
	v_mfma_f32_16x16x32_bf16 v[100:103], v[158:161], v[20:23], v[64:67]
	v_mfma_f32_16x16x32_bf16 v[96:99], v[230:233], v[20:23], v[166:169]
	ds_read_b128 v[20:23], v29
	s_waitcnt lgkmcnt(3)
	v_mfma_f32_16x16x32_bf16 v[92:95], v[8:11], v[52:55], v[72:75]
	v_mfma_f32_16x16x32_bf16 v[88:91], v[154:157], v[52:55], v[76:79]
	v_mfma_f32_16x16x32_bf16 v[84:87], v[158:161], v[52:55], v[80:83]
	v_mfma_f32_16x16x32_bf16 v[80:83], v[230:233], v[52:55], v[32:35]
	ds_read_b128 v[166:169], v30
	s_waitcnt lgkmcnt(3)
	v_mfma_f32_16x16x32_bf16 v[76:79], v[8:11], v[24:27], v[214:217]
	v_mfma_f32_16x16x32_bf16 v[72:75], v[154:157], v[24:27], v[218:221]
	v_mfma_f32_16x16x32_bf16 v[68:71], v[158:161], v[24:27], v[222:225]
	v_mfma_f32_16x16x32_bf16 v[64:67], v[230:233], v[24:27], v[12:15]
	ds_read_b128 v[214:217], v31
	s_waitcnt lgkmcnt(3)
	v_mfma_f32_16x16x32_bf16 v[60:63], v[8:11], v[16:19], v[36:39]
	v_mfma_f32_16x16x32_bf16 v[56:59], v[154:157], v[16:19], v[226:229]
	v_mfma_f32_16x16x32_bf16 v[52:55], v[158:161], v[16:19], v[112:115]
	v_mfma_f32_16x16x32_bf16 v[48:51], v[230:233], v[16:19], v[174:177]
	s_waitcnt lgkmcnt(2)
	v_mfma_f32_16x16x32_bf16 v[44:47], v[8:11], v[20:23], v[116:119]
	v_mfma_f32_16x16x32_bf16 v[40:43], v[154:157], v[20:23], v[120:123]
	v_mfma_f32_16x16x32_bf16 v[36:39], v[158:161], v[20:23], v[124:127]
	v_mfma_f32_16x16x32_bf16 v[32:35], v[230:233], v[20:23], v[170:173]
	s_waitcnt lgkmcnt(1)
	v_mfma_f32_16x16x32_bf16 v[28:31], v[8:11], v[166:169], v[128:131]
	v_mfma_f32_16x16x32_bf16 v[24:27], v[154:157], v[166:169], v[132:135]
	v_mfma_f32_16x16x32_bf16 v[20:23], v[158:161], v[166:169], v[136:139]
	v_mfma_f32_16x16x32_bf16 v[16:19], v[230:233], v[166:169], v[178:181]
	s_waitcnt lgkmcnt(0)
	v_mfma_f32_16x16x32_bf16 v[12:15], v[8:11], v[214:217], v[0:3]
	v_mfma_f32_16x16x32_bf16 v[8:11], v[154:157], v[214:217], v[4:7]
	v_mfma_f32_16x16x32_bf16 v[4:7], v[158:161], v[214:217], v[140:143]
	v_mfma_f32_16x16x32_bf16 v[0:3], v[230:233], v[214:217], v[150:153]
	v_mov_b32_e32 v145, v184
	s_waitcnt vmcnt(0)
	s_barrier
	s_lshl_b32 s20, s13, 8
	s_lshl_b32 s14, s12, 8
	v_and_b32_e32 v151, 15, v145
	v_ashrrev_i32_e32 v112, 1, v145
	v_and_b32_e32 v153, 0xffffff80, v112
	v_or_b32_e32 v112, s20, v151
	v_add_u32_e32 v112, v112, v153
	v_ashrrev_i32_e32 v113, 31, v112
	v_lshlrev_b64 v[112:113], 13, v[112:113]
	v_bfe_u32 v150, v145, 6, 2
	v_lshl_add_u64 v[112:113], s[4:5], 0, v[112:113]
	s_ashr_i32 s15, s14, 31
	v_bfe_u32 v152, v145, 4, 2
	v_lshl_add_u64 v[112:113], s[14:15], 2, v[112:113]
	v_lshlrev_b32_e32 v146, 8, v150
	v_lshl_add_u64 v[112:113], v[112:113], 0, v[146:147]
	v_lshlrev_b32_e32 v146, 4, v152
	v_lshl_add_u64 v[154:155], v[112:113], 0, v[146:147]
	global_load_dwordx4 v[120:123], v[154:155], off offset:192
	global_load_dwordx4 v[128:131], v[154:155], off offset:128
	global_load_dwordx4 v[136:139], v[154:155], off offset:64
	global_load_dwordx4 v[140:143], v[154:155], off
	v_add_co_u32_e32 v112, vcc, s66, v154
	v_lshlrev_b32_e32 v158, 2, v152
	s_nop 0
	v_addc_co_u32_e32 v113, vcc, 0, v155, vcc
	global_load_dwordx4 v[132:135], v[112:113], off
	global_load_dwordx4 v[124:127], v[112:113], off offset:64
	global_load_dwordx4 v[116:119], v[112:113], off offset:128
	v_cmp_lt_i32_e32 vcc, v188, v186
	global_load_dwordx4 v[112:115], v[112:113], off offset:192
	v_cmp_eq_u32_e64 s[0:1], 0, v152
	v_cndmask_b32_e32 v146, v185, v188, vcc
	v_cmp_lt_i32_e32 vcc, v187, v186
	v_lshlrev_b32_e32 v149, 2, v146
	v_lshlrev_b32_e32 v157, 6, v150
	v_cndmask_b32_e32 v156, v185, v187, vcc
	v_lshlrev_b32_e32 v146, 2, v156
	v_or_b32_e32 v156, v153, v151
	v_add_u32_e32 v152, s20, v156
	v_ashrrev_i32_e32 v153, 31, v152
	v_lshl_or_b32 v182, v150, 10, v204
	v_or3_b32 v150, v157, s14, v158
	v_lshlrev_b64 v[158:159], 13, v[152:153]
	v_ashrrev_i32_e32 v151, 31, v150
	v_lshlrev_b64 v[160:161], 12, v[152:153]
	v_lshl_add_u64 v[158:159], s[4:5], 0, v[158:159]
	v_lshl_add_u64 v[160:161], s[6:7], 0, v[160:161]
	v_lshl_add_u64 v[166:167], v[150:151], 2, v[158:159]
	v_lshl_add_u64 v[168:169], v[150:151], 1, v[160:161]
	s_waitcnt vmcnt(7)
	v_pk_add_f32 v[158:159], v[162:163], v[120:121]
	s_waitcnt vmcnt(6)
	v_pk_add_f32 v[120:121], v[242:243], v[128:129]
	s_waitcnt vmcnt(5)
	v_pk_add_f32 v[128:129], v[238:239], v[136:137]
	s_waitcnt vmcnt(4)
	v_pk_add_f32 v[136:137], v[234:235], v[140:141]
	v_pk_add_f32 v[160:161], v[164:165], v[122:123]
	v_pk_add_f32 v[122:123], v[244:245], v[130:131]
	v_pk_add_f32 v[130:131], v[240:241], v[138:139]
	v_pk_add_f32 v[138:139], v[236:237], v[142:143]
	v_pk_mul_f32 v[172:173], v[128:129], v[128:129]
	v_pk_mul_f32 v[178:179], v[136:137], v[136:137]
	v_pk_mul_f32 v[162:163], v[120:121], v[120:121]
	v_pk_mul_f32 v[174:175], v[130:131], v[130:131]
	v_cvt_pk_bf16_f32 v176, v136, v137
	v_pk_mul_f32 v[180:181], v[138:139], v[138:139]
	global_store_dwordx4 v[166:167], v[136:139], off
	v_add_f32_e32 v153, v172, v173
	v_add_f32_e32 v157, v178, v179
	v_pk_mul_f32 v[136:137], v[158:159], v[158:159]
	v_pk_mul_f32 v[164:165], v[122:123], v[122:123]
	v_cvt_pk_bf16_f32 v177, v138, v139
	v_pk_mul_f32 v[138:139], v[160:161], v[160:161]
	v_add_f32_e32 v162, v162, v163
	v_add_f32_e32 v136, v136, v137
	v_add_f32_e32 v137, v174, v153
	v_add_f32_e32 v153, v180, v157
	v_add_f32_e32 v157, v164, v162
	v_add_f32_e32 v136, v138, v136
	v_add_f32_e32 v137, v175, v137
	v_add_f32_e32 v138, v181, v153
	v_add_f32_e32 v153, v165, v157
	v_add_f32_e32 v137, v138, v137
	v_add_f32_e32 v137, v137, v153
	v_add_f32_e32 v136, v139, v136
	v_add_f32_e32 v136, v137, v136
	ds_bpermute_b32 v137, v149, v136
	v_cvt_pk_bf16_f32 v170, v128, v129
	v_cvt_pk_bf16_f32 v171, v130, v131
	v_cvt_pk_bf16_f32 v142, v120, v121
	global_store_dwordx2 v[168:169], v[176:177], off
	global_store_dwordx4 v[166:167], v[128:131], off offset:64
	global_store_dwordx2 v[168:169], v[170:171], off offset:32
	global_store_dwordx4 v[166:167], v[120:123], off offset:128
	v_cvt_pk_bf16_f32 v140, v158, v159
	v_cvt_pk_bf16_f32 v141, v160, v161
	s_waitcnt lgkmcnt(0)
	v_add_f32_e32 v120, v136, v137
	ds_bpermute_b32 v121, v146, v120
	v_cvt_pk_bf16_f32 v143, v122, v123
	v_lshl_add_u32 v153, v156, 2, v182
	global_store_dwordx2 v[168:169], v[142:143], off offset:64
	global_store_dwordx4 v[166:167], v[158:161], off offset:192
	global_store_dwordx2 v[168:169], v[140:141], off offset:96
	s_and_saveexec_b64 s[14:15], s[0:1]
	s_cbranch_execz .LBB0_567
	s_waitcnt lgkmcnt(0)
	v_add_f32_e32 v120, v120, v121
	ds_write_b32 v153, v120

.LBB0_626:
	s_ashr_i32 s43, s42, 31
	s_lshl_b64 s[42:43], s[42:43], 20
	s_add_u32 s42, s58, s42
	s_addc_u32 s43, s62, s43
	s_ashr_i32 s5, s4, 31
	v_lshlrev_b32_e32 v3, 6, v1
	s_lshl_b64 s[4:5], s[4:5], 20
	v_and_b32_e32 v2, 48, v1
	v_and_b32_e32 v4, 0x3c0, v3
	v_lshlrev_b32_e32 v1, 2, v1
	s_add_u32 s4, s54, s4
	v_or_b32_e32 v5, v4, v2
	v_and_b32_e32 v1, 32, v1
	v_lshlrev_b32_e32 v0, 13, v0
	s_mov_b32 s80, 0x18000
	s_addc_u32 s5, s55, s5
	v_and_b32_e32 v111, 0x6000, v0
	s_add_i32 s46, s1, 0x10000
	s_add_i32 s47, s1, 0x18000
	s_add_i32 s74, s1, 0x12000
	s_add_i32 s75, s1, 0x1a000
	s_add_i32 s76, s1, 0x14000
	s_add_i32 s77, s1, 0x1c000
	s_add_i32 s78, s1, 0x16000
	s_add_i32 s79, s1, 0x1e000
	v_bitop3_b32 v0, v5, s80, v1 bitop3:0xde
	s_mov_b32 s80, 0x10400
	v_bitop3_b32 v149, v5, s80, v1 bitop3:0xde
	s_add_u32 s80, s52, s2
	s_addc_u32 s81, s53, s3
	s_add_i32 s2, s82, s83
	s_ashr_i32 s3, s2, 31
	s_waitcnt vmcnt(0)
	s_lshl_b64 s[2:3], s[2:3], 20
	v_bitop3_b32 v110, v4, v1, v2 bitop3:0x36
	v_and_b32_e32 v112, 0xffffc000, v3
	s_add_u32 s82, s10, s2
	v_mov_b32_e32 v4, 0
	v_or_b32_e32 v113, 0x800, v112
	v_or_b32_e32 v114, 0x1000, v112
	v_or_b32_e32 v115, 0x1800, v112
	v_or_b32_e32 v116, 0x2000, v112
	v_or_b32_e32 v117, 0x2800, v112
	v_or_b32_e32 v118, 0x3000, v112
	v_or_b32_e32 v119, 0x3800, v112
	v_bitop3_b32 v145, v5, s33, v1 bitop3:0xde
	s_addc_u32 s83, s11, s3
	s_mov_b64 s[2:3], 0
	s_mov_b32 s84, 1
	v_add_u32_e32 v150, v0, v111
	v_mov_b32_e32 v5, v4
	v_mov_b32_e32 v6, v4
	v_mov_b32_e32 v7, v4
	v_mov_b32_e32 v72, v4
	v_mov_b32_e32 v73, v4
	v_mov_b32_e32 v74, v4
	v_mov_b32_e32 v75, v4
	v_mov_b32_e32 v12, v4
	v_mov_b32_e32 v13, v4
	v_mov_b32_e32 v14, v4
	v_mov_b32_e32 v15, v4
	v_mov_b32_e32 v76, v4
	v_mov_b32_e32 v77, v4
	v_mov_b32_e32 v78, v4
	v_mov_b32_e32 v79, v4
	v_mov_b32_e32 v16, v4
	v_mov_b32_e32 v17, v4
	v_mov_b32_e32 v18, v4
	v_mov_b32_e32 v19, v4
	v_mov_b32_e32 v80, v4
	v_mov_b32_e32 v81, v4
	v_mov_b32_e32 v82, v4
	v_mov_b32_e32 v83, v4
	v_mov_b32_e32 v20, v4
	v_mov_b32_e32 v21, v4
	v_mov_b32_e32 v22, v4
	v_mov_b32_e32 v23, v4
	v_mov_b32_e32 v84, v4
	v_mov_b32_e32 v85, v4
	v_mov_b32_e32 v86, v4
	v_mov_b32_e32 v87, v4
	v_mov_b32_e32 v24, v4
	v_mov_b32_e32 v25, v4
	v_mov_b32_e32 v26, v4
	v_mov_b32_e32 v27, v4
	v_mov_b32_e32 v88, v4
	v_mov_b32_e32 v89, v4
	v_mov_b32_e32 v90, v4
	v_mov_b32_e32 v91, v4
	v_mov_b32_e32 v28, v4
	v_mov_b32_e32 v29, v4
	v_mov_b32_e32 v30, v4
	v_mov_b32_e32 v31, v4
	v_mov_b32_e32 v92, v4
	v_mov_b32_e32 v93, v4
	v_mov_b32_e32 v94, v4
	v_mov_b32_e32 v95, v4
	v_mov_b32_e32 v32, v4
	v_mov_b32_e32 v33, v4
	v_mov_b32_e32 v34, v4
	v_mov_b32_e32 v35, v4
	v_mov_b32_e32 v96, v4
	v_mov_b32_e32 v97, v4
	v_mov_b32_e32 v98, v4
	v_mov_b32_e32 v99, v4
	v_mov_b32_e32 v36, v4
	v_mov_b32_e32 v37, v4
	v_mov_b32_e32 v38, v4
	v_mov_b32_e32 v39, v4
	v_mov_b32_e32 v100, v4
	v_mov_b32_e32 v101, v4
	v_mov_b32_e32 v102, v4
	v_mov_b32_e32 v103, v4
	v_mov_b32_e32 v40, v4
	v_mov_b32_e32 v41, v4
	v_mov_b32_e32 v42, v4
	v_mov_b32_e32 v43, v4
	v_mov_b32_e32 v120, v4
	v_mov_b32_e32 v121, v4
	v_mov_b32_e32 v122, v4
	v_mov_b32_e32 v123, v4
	v_mov_b32_e32 v44, v4
	v_mov_b32_e32 v45, v4
	v_mov_b32_e32 v46, v4
	v_mov_b32_e32 v47, v4
	v_mov_b32_e32 v124, v4
	v_mov_b32_e32 v125, v4
	v_mov_b32_e32 v126, v4
	v_mov_b32_e32 v127, v4
	v_mov_b32_e32 v48, v4
	v_mov_b32_e32 v49, v4
	v_mov_b32_e32 v50, v4
	v_mov_b32_e32 v51, v4
	v_mov_b32_e32 v128, v4
	v_mov_b32_e32 v129, v4
	v_mov_b32_e32 v130, v4
	v_mov_b32_e32 v131, v4
	v_mov_b32_e32 v52, v4
	v_mov_b32_e32 v53, v4
	v_mov_b32_e32 v54, v4
	v_mov_b32_e32 v55, v4
	v_mov_b32_e32 v132, v4
	v_mov_b32_e32 v133, v4
	v_mov_b32_e32 v134, v4
	v_mov_b32_e32 v135, v4
	v_mov_b32_e32 v56, v4
	v_mov_b32_e32 v57, v4
	v_mov_b32_e32 v58, v4
	v_mov_b32_e32 v59, v4
	v_mov_b32_e32 v136, v4
	v_mov_b32_e32 v137, v4
	v_mov_b32_e32 v138, v4
	v_mov_b32_e32 v139, v4
	v_mov_b32_e32 v60, v4
	v_mov_b32_e32 v61, v4
	v_mov_b32_e32 v62, v4
	v_mov_b32_e32 v63, v4
	v_mov_b32_e32 v140, v4
	v_mov_b32_e32 v141, v4
	v_mov_b32_e32 v142, v4
	v_mov_b32_e32 v143, v4
	v_mov_b32_e32 v64, v4
	v_mov_b32_e32 v65, v4
	v_mov_b32_e32 v66, v4
	v_mov_b32_e32 v67, v4
	v_mov_b32_e32 v0, v4
	v_mov_b32_e32 v1, v4
	v_mov_b32_e32 v2, v4
	v_mov_b32_e32 v3, v4
	v_mov_b32_e32 v68, v4
	v_mov_b32_e32 v69, v4
	v_mov_b32_e32 v70, v4
	v_mov_b32_e32 v71, v4
	v_mov_b32_e32 v8, v4
	v_mov_b32_e32 v9, v4
	v_mov_b32_e32 v10, v4
	v_mov_b32_e32 v11, v4
	s_waitcnt lgkmcnt(0)
	s_barrier
	s_add_u32 s85, s82, s2
	s_addc_u32 s90, s83, s3
	s_add_u32 s86, s85, 0x1b900080
	s_addc_u32 s87, s90, 0
	s_add_u32 s91, s80, s2
	s_addc_u32 s92, s81, s3
	s_add_u32 s88, s91, 0x3400080
	s_addc_u32 s89, s92, 0
	v_add_u32_e32 v151, v110, v111
	v_add_u32_e32 v189, v110, v112
	ds_read_b128 v[152:155], v151 offset:32768
	ds_read_b128 v[156:159], v189
	ds_read_b128 v[160:163], v151 offset:34816
	ds_read_b128 v[164:167], v189 offset:2048
	ds_read_b128 v[168:171], v151 offset:36864
	ds_read_b128 v[172:175], v151 offset:38912
	ds_read_b128 v[176:179], v189 offset:4096
	ds_read_b128 v[180:183], v189 offset:6144
	s_branch .Lmy_rot_627
.LBB0_627:
	s_add_u32 s85, s82, s2
	s_addc_u32 s90, s83, s3
	s_add_u32 s86, s85, 0x1b900080
	s_addc_u32 s87, s90, 0
	s_add_u32 s91, s80, s2
	s_addc_u32 s92, s81, s3
	s_add_u32 s88, s91, 0x3400080
	s_addc_u32 s89, s92, 0
	v_add_u32_e32 v151, v110, v111
	v_add_u32_e32 v189, v110, v112
	ds_read_b128 v[152:155], v151 offset:32768
	ds_read_b128 v[156:159], v189
	v_mfma_f32_16x16x32_bf16 v[76:79], v[160:163], v[176:179], v[76:79]
	v_mfma_f32_16x16x32_bf16 v[64:67], v[160:163], v[180:183], v[64:67]
	ds_read_b128 v[160:163], v151 offset:34816
	v_mfma_f32_16x16x32_bf16 v[12:15], v[164:167], v[176:179], v[12:15]
	v_mfma_f32_16x16x32_bf16 v[0:3], v[164:167], v[180:183], v[0:3]
	ds_read_b128 v[164:167], v189 offset:2048
	v_mfma_f32_16x16x32_bf16 v[72:75], v[168:171], v[176:179], v[72:75]
	v_mfma_f32_16x16x32_bf16 v[68:71], v[168:171], v[180:183], v[68:71]
	ds_read_b128 v[168:171], v151 offset:36864
	v_mfma_f32_16x16x32_bf16 v[4:7], v[172:175], v[176:179], v[4:7]
	v_mfma_f32_16x16x32_bf16 v[8:11], v[172:175], v[180:183], v[8:11]
	ds_read_b128 v[172:175], v151 offset:38912
	ds_read_b128 v[176:179], v189 offset:4096
	ds_read_b128 v[180:183], v189 offset:6144
.Lmy_rot_627:
	s_waitcnt lgkmcnt(6)
	v_mfma_f32_16x16x32_bf16 v[140:143], v[152:155], v[156:159], v[140:143]
	s_waitcnt lgkmcnt(5)
	v_mfma_f32_16x16x32_bf16 v[60:63], v[160:163], v[156:159], v[60:63]
	s_waitcnt lgkmcnt(4)
	s_mov_b32 m0, s46
	v_mfma_f32_16x16x32_bf16 v[132:135], v[152:155], v[164:167], v[132:135]
	global_load_lds_dwordx4 v104, s[86:87]
	v_mfma_f32_16x16x32_bf16 v[52:55], v[160:163], v[164:167], v[52:55]
	s_waitcnt lgkmcnt(3)
	v_mfma_f32_16x16x32_bf16 v[136:139], v[168:171], v[156:159], v[136:139]
	v_mfma_f32_16x16x32_bf16 v[128:131], v[168:171], v[164:167], v[128:131]
	s_waitcnt lgkmcnt(2)
	s_mov_b32 m0, s47
	v_mfma_f32_16x16x32_bf16 v[56:59], v[172:175], v[156:159], v[56:59]
	global_load_lds_dwordx4 v104, s[88:89]
	ds_read_b128 v[156:159], v189 offset:8192
	v_mfma_f32_16x16x32_bf16 v[48:51], v[172:175], v[164:167], v[48:51]
	ds_read_b128 v[164:167], v189 offset:10240
	s_waitcnt lgkmcnt(3)
	v_mfma_f32_16x16x32_bf16 v[124:127], v[152:155], v[176:179], v[124:127]
	v_mfma_f32_16x16x32_bf16 v[44:47], v[160:163], v[176:179], v[44:47]
	s_mov_b32 m0, s74
	v_mfma_f32_16x16x32_bf16 v[120:123], v[168:171], v[176:179], v[120:123]
	global_load_lds_dwordx4 v106, s[86:87]
	v_mfma_f32_16x16x32_bf16 v[40:43], v[172:175], v[176:179], v[40:43]
	ds_read_b128 v[176:179], v189 offset:12288
	s_waitcnt lgkmcnt(3)
	v_mfma_f32_16x16x32_bf16 v[100:103], v[152:155], v[180:183], v[100:103]
	v_mfma_f32_16x16x32_bf16 v[36:39], v[160:163], v[180:183], v[36:39]
	s_mov_b32 m0, s75
	v_mfma_f32_16x16x32_bf16 v[96:99], v[168:171], v[180:183], v[96:99]
	global_load_lds_dwordx4 v106, s[88:89]
	v_mfma_f32_16x16x32_bf16 v[32:35], v[172:175], v[180:183], v[32:35]
	ds_read_b128 v[180:183], v189 offset:14336
	s_waitcnt lgkmcnt(3)
	v_mfma_f32_16x16x32_bf16 v[28:31], v[160:163], v[156:159], v[28:31]
	s_waitcnt lgkmcnt(2)
	v_mfma_f32_16x16x32_bf16 v[20:23], v[160:163], v[164:167], v[20:23]
	s_waitcnt lgkmcnt(1)
	s_mov_b32 m0, s76
	v_mfma_f32_16x16x32_bf16 v[12:15], v[160:163], v[176:179], v[12:15]
	global_load_lds_dwordx4 v108, s[86:87]
	s_waitcnt lgkmcnt(0)
	v_mfma_f32_16x16x32_bf16 v[0:3], v[160:163], v[180:183], v[0:3]
	ds_read_b128 v[160:163], v151 offset:33792
	v_mfma_f32_16x16x32_bf16 v[92:95], v[152:155], v[156:159], v[92:95]
	v_mfma_f32_16x16x32_bf16 v[84:87], v[152:155], v[164:167], v[84:87]
	s_mov_b32 m0, s77
	v_mfma_f32_16x16x32_bf16 v[76:79], v[152:155], v[176:179], v[76:79]
	global_load_lds_dwordx4 v108, s[88:89]
	v_mfma_f32_16x16x32_bf16 v[64:67], v[152:155], v[180:183], v[64:67]
	ds_read_b128 v[152:155], v189 offset:1024
	v_mfma_f32_16x16x32_bf16 v[80:83], v[168:171], v[164:167], v[80:83]
	v_mfma_f32_16x16x32_bf16 v[16:19], v[172:175], v[164:167], v[16:19]
	ds_read_b128 v[164:167], v151 offset:35840
	s_mov_b32 m0, s78
	v_mfma_f32_16x16x32_bf16 v[88:91], v[168:171], v[156:159], v[88:91]
	global_load_lds_dwordx4 v146, s[86:87]
	v_mfma_f32_16x16x32_bf16 v[24:27], v[172:175], v[156:159], v[24:27]
	ds_read_b128 v[156:159], v189 offset:3072
	v_mfma_f32_16x16x32_bf16 v[72:75], v[168:171], v[176:179], v[72:75]
	v_mfma_f32_16x16x32_bf16 v[4:7], v[172:175], v[176:179], v[4:7]
	ds_read_b128 v[176:179], v189 offset:5120
	s_mov_b32 m0, s79
	v_mfma_f32_16x16x32_bf16 v[68:71], v[168:171], v[180:183], v[68:71]
	global_load_lds_dwordx4 v146, s[88:89]
	ds_read_b128 v[168:171], v151 offset:37888
	v_mfma_f32_16x16x32_bf16 v[8:11], v[172:175], v[180:183], v[8:11]
	ds_read_b128 v[172:175], v151 offset:39936
	ds_read_b128 v[180:183], v189 offset:7168
	s_waitcnt lgkmcnt(6)
	v_mfma_f32_16x16x32_bf16 v[140:143], v[160:163], v[152:155], v[140:143]
	s_waitcnt lgkmcnt(5)
	v_mfma_f32_16x16x32_bf16 v[60:63], v[164:167], v[152:155], v[60:63]
	s_waitcnt lgkmcnt(4)
	v_mfma_f32_16x16x32_bf16 v[132:135], v[160:163], v[156:159], v[132:135]
	v_mfma_f32_16x16x32_bf16 v[52:55], v[164:167], v[156:159], v[52:55]
	s_waitcnt lgkmcnt(3)
	v_mfma_f32_16x16x32_bf16 v[124:127], v[160:163], v[176:179], v[124:127]
	v_mfma_f32_16x16x32_bf16 v[44:47], v[164:167], v[176:179], v[44:47]
	s_waitcnt lgkmcnt(2)
	v_mfma_f32_16x16x32_bf16 v[136:139], v[168:171], v[152:155], v[136:139]
	s_waitcnt lgkmcnt(1)
	v_mfma_f32_16x16x32_bf16 v[56:59], v[172:175], v[152:155], v[56:59]
	ds_read_b128 v[152:155], v189 offset:9216
	v_mfma_f32_16x16x32_bf16 v[128:131], v[168:171], v[156:159], v[128:131]
	v_mfma_f32_16x16x32_bf16 v[48:51], v[172:175], v[156:159], v[48:51]
	ds_read_b128 v[156:159], v189 offset:11264
	v_mfma_f32_16x16x32_bf16 v[120:123], v[168:171], v[176:179], v[120:123]
	v_mfma_f32_16x16x32_bf16 v[40:43], v[172:175], v[176:179], v[40:43]
	ds_read_b128 v[176:179], v189 offset:13312
	s_waitcnt lgkmcnt(3)
	v_mfma_f32_16x16x32_bf16 v[100:103], v[160:163], v[180:183], v[100:103]
	v_mfma_f32_16x16x32_bf16 v[36:39], v[164:167], v[180:183], v[36:39]
	v_mfma_f32_16x16x32_bf16 v[96:99], v[168:171], v[180:183], v[96:99]
	v_mfma_f32_16x16x32_bf16 v[32:35], v[172:175], v[180:183], v[32:35]
	ds_read_b128 v[180:183], v189 offset:15360
	s_waitcnt lgkmcnt(3)
	v_mfma_f32_16x16x32_bf16 v[92:95], v[160:163], v[152:155], v[92:95]
	v_mfma_f32_16x16x32_bf16 v[28:31], v[164:167], v[152:155], v[28:31]
	v_mfma_f32_16x16x32_bf16 v[88:91], v[168:171], v[152:155], v[88:91]
	v_mfma_f32_16x16x32_bf16 v[24:27], v[172:175], v[152:155], v[24:27]
	s_waitcnt lgkmcnt(2)
	v_mfma_f32_16x16x32_bf16 v[84:87], v[160:163], v[156:159], v[84:87]
	v_mfma_f32_16x16x32_bf16 v[20:23], v[164:167], v[156:159], v[20:23]
	v_mfma_f32_16x16x32_bf16 v[80:83], v[168:171], v[156:159], v[80:83]
	v_mfma_f32_16x16x32_bf16 v[16:19], v[172:175], v[156:159], v[16:19]
	s_add_u32 s85, s85, 0x1b900100
	s_addc_u32 s86, s90, 0
	s_add_u32 s88, s91, 0x3400100
	s_addc_u32 s89, s92, 0
	s_cmp_lt_u32 s84, 31
	s_cselect_b32 s87, s86, s43
	s_cselect_b32 s86, s85, s42
	s_waitcnt vmcnt(0)
	s_waitcnt lgkmcnt(0)
	s_barrier
	s_cselect_b32 s89, s89, s5
	s_cselect_b32 s88, s88, s4
	ds_read_b128 v[152:155], v150
	v_add_u32_e32 v151, v145, v112
	ds_read_b128 v[156:159], v151
	v_mfma_f32_16x16x32_bf16 v[76:79], v[160:163], v[176:179], v[76:79]
	v_mfma_f32_16x16x32_bf16 v[64:67], v[160:163], v[180:183], v[64:67]
	ds_read_b128 v[160:163], v150 offset:2048
	v_mfma_f32_16x16x32_bf16 v[12:15], v[164:167], v[176:179], v[12:15]
	v_mfma_f32_16x16x32_bf16 v[0:3], v[164:167], v[180:183], v[0:3]
	v_add_u32_e32 v151, v145, v113
	ds_read_b128 v[164:167], v151
	v_mfma_f32_16x16x32_bf16 v[72:75], v[168:171], v[176:179], v[72:75]
	v_mfma_f32_16x16x32_bf16 v[68:71], v[168:171], v[180:183], v[68:71]
	ds_read_b128 v[168:171], v150 offset:4096
	v_mfma_f32_16x16x32_bf16 v[4:7], v[172:175], v[176:179], v[4:7]
	v_mfma_f32_16x16x32_bf16 v[8:11], v[172:175], v[180:183], v[8:11]
	ds_read_b128 v[172:175], v150 offset:6144
	v_add_u32_e32 v151, v145, v114
	ds_read_b128 v[176:179], v151
	v_add_u32_e32 v151, v145, v115
	ds_read_b128 v[180:183], v151
	s_waitcnt lgkmcnt(6)
	v_mfma_f32_16x16x32_bf16 v[140:143], v[152:155], v[156:159], v[140:143]
	s_waitcnt lgkmcnt(5)
	v_mfma_f32_16x16x32_bf16 v[60:63], v[160:163], v[156:159], v[60:63]
	s_waitcnt lgkmcnt(4)
	s_mov_b32 m0, s1
	v_mfma_f32_16x16x32_bf16 v[132:135], v[152:155], v[164:167], v[132:135]
	global_load_lds_dwordx4 v104, s[86:87]
	v_mfma_f32_16x16x32_bf16 v[52:55], v[160:163], v[164:167], v[52:55]
	s_waitcnt lgkmcnt(3)
	v_mfma_f32_16x16x32_bf16 v[136:139], v[168:171], v[156:159], v[136:139]
	v_mfma_f32_16x16x32_bf16 v[128:131], v[168:171], v[164:167], v[128:131]
	s_waitcnt lgkmcnt(2)
	s_mov_b32 m0, s45
	v_mfma_f32_16x16x32_bf16 v[56:59], v[172:175], v[156:159], v[56:59]
	global_load_lds_dwordx4 v104, s[88:89]
	v_add_u32_e32 v151, v145, v116
	ds_read_b128 v[156:159], v151
	v_mfma_f32_16x16x32_bf16 v[48:51], v[172:175], v[164:167], v[48:51]
	v_add_u32_e32 v151, v145, v117
	ds_read_b128 v[164:167], v151
	s_waitcnt lgkmcnt(3)
	v_mfma_f32_16x16x32_bf16 v[124:127], v[152:155], v[176:179], v[124:127]
	v_mfma_f32_16x16x32_bf16 v[44:47], v[160:163], v[176:179], v[44:47]
	s_mov_b32 m0, s68
	v_mfma_f32_16x16x32_bf16 v[120:123], v[168:171], v[176:179], v[120:123]
	global_load_lds_dwordx4 v106, s[86:87]
	v_mfma_f32_16x16x32_bf16 v[40:43], v[172:175], v[176:179], v[40:43]
	v_add_u32_e32 v151, v145, v118
	ds_read_b128 v[176:179], v151
	s_waitcnt lgkmcnt(3)
	v_mfma_f32_16x16x32_bf16 v[100:103], v[152:155], v[180:183], v[100:103]
	v_mfma_f32_16x16x32_bf16 v[36:39], v[160:163], v[180:183], v[36:39]
	s_mov_b32 m0, s69
	v_mfma_f32_16x16x32_bf16 v[96:99], v[168:171], v[180:183], v[96:99]
	global_load_lds_dwordx4 v106, s[88:89]
	v_mfma_f32_16x16x32_bf16 v[32:35], v[172:175], v[180:183], v[32:35]
	v_add_u32_e32 v151, v145, v119
	ds_read_b128 v[180:183], v151
	s_waitcnt lgkmcnt(3)
	v_mfma_f32_16x16x32_bf16 v[28:31], v[160:163], v[156:159], v[28:31]
	s_waitcnt lgkmcnt(2)
	v_mfma_f32_16x16x32_bf16 v[20:23], v[160:163], v[164:167], v[20:23]
	s_waitcnt lgkmcnt(1)
	s_mov_b32 m0, s70
	v_mfma_f32_16x16x32_bf16 v[12:15], v[160:163], v[176:179], v[12:15]
	global_load_lds_dwordx4 v108, s[86:87]
	s_waitcnt lgkmcnt(0)
	v_mfma_f32_16x16x32_bf16 v[0:3], v[160:163], v[180:183], v[0:3]
	ds_read_b128 v[160:163], v150 offset:1024
	v_mfma_f32_16x16x32_bf16 v[92:95], v[152:155], v[156:159], v[92:95]
	v_mfma_f32_16x16x32_bf16 v[84:87], v[152:155], v[164:167], v[84:87]
	s_mov_b32 m0, s71
	v_mfma_f32_16x16x32_bf16 v[76:79], v[152:155], v[176:179], v[76:79]
	global_load_lds_dwordx4 v108, s[88:89]
	v_mfma_f32_16x16x32_bf16 v[64:67], v[152:155], v[180:183], v[64:67]
	v_add_u32_e32 v151, v149, v112
	ds_read_b128 v[152:155], v151
	v_mfma_f32_16x16x32_bf16 v[80:83], v[168:171], v[164:167], v[80:83]
	v_mfma_f32_16x16x32_bf16 v[16:19], v[172:175], v[164:167], v[16:19]
	ds_read_b128 v[164:167], v150 offset:3072
	s_mov_b32 m0, s72
	v_mfma_f32_16x16x32_bf16 v[88:91], v[168:171], v[156:159], v[88:91]
	global_load_lds_dwordx4 v146, s[86:87]
	v_mfma_f32_16x16x32_bf16 v[24:27], v[172:175], v[156:159], v[24:27]
	v_add_u32_e32 v151, v149, v113
	ds_read_b128 v[156:159], v151
	v_mfma_f32_16x16x32_bf16 v[72:75], v[168:171], v[176:179], v[72:75]
	v_mfma_f32_16x16x32_bf16 v[4:7], v[172:175], v[176:179], v[4:7]
	v_add_u32_e32 v151, v149, v114
	ds_read_b128 v[176:179], v151
	s_mov_b32 m0, s73
	v_mfma_f32_16x16x32_bf16 v[68:71], v[168:171], v[180:183], v[68:71]
	global_load_lds_dwordx4 v146, s[88:89]
	ds_read_b128 v[168:171], v150 offset:5120
	v_mfma_f32_16x16x32_bf16 v[8:11], v[172:175], v[180:183], v[8:11]
	ds_read_b128 v[172:175], v150 offset:7168
	v_add_u32_e32 v151, v149, v115
	ds_read_b128 v[180:183], v151
	s_waitcnt lgkmcnt(6)
	v_mfma_f32_16x16x32_bf16 v[140:143], v[160:163], v[152:155], v[140:143]
	s_waitcnt lgkmcnt(5)
	v_mfma_f32_16x16x32_bf16 v[60:63], v[164:167], v[152:155], v[60:63]
	s_waitcnt lgkmcnt(4)
	v_mfma_f32_16x16x32_bf16 v[132:135], v[160:163], v[156:159], v[132:135]
	v_mfma_f32_16x16x32_bf16 v[52:55], v[164:167], v[156:159], v[52:55]
	s_waitcnt lgkmcnt(3)
	v_mfma_f32_16x16x32_bf16 v[124:127], v[160:163], v[176:179], v[124:127]
	v_mfma_f32_16x16x32_bf16 v[44:47], v[164:167], v[176:179], v[44:47]
	s_waitcnt lgkmcnt(2)
	v_mfma_f32_16x16x32_bf16 v[136:139], v[168:171], v[152:155], v[136:139]
	s_waitcnt lgkmcnt(1)
	v_mfma_f32_16x16x32_bf16 v[56:59], v[172:175], v[152:155], v[56:59]
	v_add_u32_e32 v151, v149, v116
	ds_read_b128 v[152:155], v151
	v_mfma_f32_16x16x32_bf16 v[128:131], v[168:171], v[156:159], v[128:131]
	v_mfma_f32_16x16x32_bf16 v[48:51], v[172:175], v[156:159], v[48:51]
	v_add_u32_e32 v151, v149, v117
	ds_read_b128 v[156:159], v151
	v_mfma_f32_16x16x32_bf16 v[120:123], v[168:171], v[176:179], v[120:123]
	v_mfma_f32_16x16x32_bf16 v[40:43], v[172:175], v[176:179], v[40:43]
	v_add_u32_e32 v151, v149, v118
	ds_read_b128 v[176:179], v151
	s_waitcnt lgkmcnt(3)
	v_mfma_f32_16x16x32_bf16 v[100:103], v[160:163], v[180:183], v[100:103]
	v_mfma_f32_16x16x32_bf16 v[36:39], v[164:167], v[180:183], v[36:39]
	v_mfma_f32_16x16x32_bf16 v[96:99], v[168:171], v[180:183], v[96:99]
	v_mfma_f32_16x16x32_bf16 v[32:35], v[172:175], v[180:183], v[32:35]
	v_add_u32_e32 v151, v149, v119
	ds_read_b128 v[180:183], v151
	s_waitcnt lgkmcnt(3)
	v_mfma_f32_16x16x32_bf16 v[92:95], v[160:163], v[152:155], v[92:95]
	v_mfma_f32_16x16x32_bf16 v[28:31], v[164:167], v[152:155], v[28:31]
	v_mfma_f32_16x16x32_bf16 v[88:91], v[168:171], v[152:155], v[88:91]
	v_mfma_f32_16x16x32_bf16 v[24:27], v[172:175], v[152:155], v[24:27]
	s_waitcnt lgkmcnt(2)
	v_mfma_f32_16x16x32_bf16 v[84:87], v[160:163], v[156:159], v[84:87]
	v_mfma_f32_16x16x32_bf16 v[20:23], v[164:167], v[156:159], v[20:23]
	v_mfma_f32_16x16x32_bf16 v[80:83], v[168:171], v[156:159], v[80:83]
	v_mfma_f32_16x16x32_bf16 v[16:19], v[172:175], v[156:159], v[16:19]
	s_waitcnt vmcnt(0)
	s_add_u32 s2, s2, 0x100
	s_addc_u32 s3, s3, 0
	s_add_i32 s84, s84, 2
	s_cmpk_lg_i32 s2, 0x1000
	s_waitcnt lgkmcnt(0)
	s_barrier
	s_cbranch_scc1 .LBB0_627
	v_mfma_f32_16x16x32_bf16 v[76:79], v[160:163], v[176:179], v[76:79]
	v_mfma_f32_16x16x32_bf16 v[64:67], v[160:163], v[180:183], v[64:67]
	v_mfma_f32_16x16x32_bf16 v[12:15], v[164:167], v[176:179], v[12:15]
	v_mfma_f32_16x16x32_bf16 v[0:3], v[164:167], v[180:183], v[0:3]
	v_mfma_f32_16x16x32_bf16 v[72:75], v[168:171], v[176:179], v[72:75]
	v_mfma_f32_16x16x32_bf16 v[68:71], v[168:171], v[180:183], v[68:71]
	v_mfma_f32_16x16x32_bf16 v[4:7], v[172:175], v[176:179], v[4:7]
	v_mfma_f32_16x16x32_bf16 v[8:11], v[172:175], v[180:183], v[8:11]
	s_nop 15
	s_nop 15
	v_mov_b32_e32 v145, v184
	s_movk_i32 s1, 0x100
	v_and_b32_e32 v167, 15, v145
	v_cmp_gt_u32_e64 s[2:3], s1, v145
	v_cmp_lt_u32_e32 vcc, 13, v167
	s_and_b64 s[4:5], s[2:3], vcc
	s_xor_b64 s[4:5], s[4:5], -1
	v_lshlrev_b32_e32 v149, 6, v167
	s_and_saveexec_b64 s[42:43], s[4:5]
	s_xor_b64 s[4:5], exec, s[42:43]
	v_lshlrev_b32_e32 v149, 6, v167
	s_or_saveexec_b64 s[4:5], s[4:5]
	v_bfe_u32 v152, v145, 4, 2
	v_readlane_b32 s68, v253, 18
	v_readlane_b32 s75, v253, 20
	s_xor_b64 exec, exec, s[4:5]
	s_cbranch_execz .LBB0_632
	v_mov_b32_e32 v104, 0x211c0
	v_lshl_or_b32 v104, v167, 2, v104
	ds_read_b32 v108, v104
	v_and_b32_e32 v104, 0xc0, v145
	v_lshl_add_u32 v104, v104, 2, v149
	v_lshl_or_b32 v109, v152, 4, v104
	v_add_u32_e32 v110, 0x1fc80, v109
	s_waitcnt lgkmcnt(0)
	v_pk_mul_f32 v[104:105], v[64:65], v[108:109] op_sel_hi:[1,0]
	v_pk_mul_f32 v[106:107], v[66:67], v[108:109] op_sel_hi:[1,0]
	v_add_u32_e32 v109, 0x1fd00, v109
	ds_write_b128 v110, v[104:107]
	v_pk_mul_f32 v[104:105], v[0:1], v[108:109] op_sel_hi:[1,0]
	v_pk_mul_f32 v[106:107], v[2:3], v[108:109] op_sel_hi:[1,0]
	ds_write_b128 v109, v[104:107]

.LBB0_696:
	s_ashr_i32 s23, s22, 31
	s_lshl_b64 s[22:23], s[22:23], 20
	s_add_u32 s22, s28, s22
	s_addc_u32 s23, s29, s23
	s_ashr_i32 s25, s24, 31
	s_lshl_b64 s[24:25], s[24:25], 20
	s_add_u32 s24, s6, s24
	s_addc_u32 s25, s7, s25
	s_add_u32 s46, s14, 0x80
	v_and_b32_e32 v8, 48, v7
	v_lshlrev_b32_e32 v9, 6, v7
	v_lshlrev_b32_e32 v7, 2, v7
	s_addc_u32 s47, s15, 0
	v_and_b32_e32 v10, 0x3c0, v9
	v_and_b32_e32 v149, 32, v7
	s_add_u32 s50, s20, 0x80
	v_or_b32_e32 v145, v10, v8
	v_bitop3_b32 v12, v10, v149, v8 bitop3:0x36
	s_waitcnt vmcnt(0)
	s_barrier
	v_lshlrev_b32_e32 v8, 13, v6
	s_addc_u32 s51, s21, 0
	s_add_i32 s27, s1, 0x10000
	v_lshl_add_u64 v[6:7], s[46:47], 0, v[0:1]
	s_mov_b32 s41, m0
	s_mov_b32 m0, s27
	s_nop 0
	global_load_lds_dwordx4 v[6:7], off
	s_mov_b32 m0, s41
	s_add_i32 s26, s1, 0x18000
	v_lshl_add_u64 v[6:7], s[50:51], 0, v[0:1]
	s_mov_b32 s41, m0
	s_mov_b32 m0, s26
	s_nop 0
	global_load_lds_dwordx4 v[6:7], off
	s_mov_b32 m0, s41
	v_lshl_add_u64 v[6:7], s[46:47], 0, v[2:3]
	s_add_i32 s41, s1, 0x12000
	s_mov_b32 s42, m0
	s_mov_b32 m0, s41
	s_nop 0
	global_load_lds_dwordx4 v[6:7], off
	s_mov_b32 m0, s42
	v_lshl_add_u64 v[6:7], s[50:51], 0, v[2:3]
	s_add_i32 s42, s1, 0x1a000
	s_mov_b32 s43, m0
	s_mov_b32 m0, s42
	s_nop 0
	global_load_lds_dwordx4 v[6:7], off
	s_mov_b32 m0, s43
	v_lshl_add_u64 v[6:7], s[46:47], 0, v[4:5]
	s_add_i32 s43, s1, 0x14000
	s_mov_b32 s44, m0
	s_mov_b32 m0, s43
	s_nop 0
	global_load_lds_dwordx4 v[6:7], off
	s_mov_b32 m0, s44
	v_lshl_add_u64 v[6:7], s[50:51], 0, v[4:5]
	s_add_i32 s44, s1, 0x1c000
	s_mov_b32 s45, m0
	s_mov_b32 m0, s44
	s_nop 0
	global_load_lds_dwordx4 v[6:7], off
	s_mov_b32 m0, s45
	v_lshl_add_u64 v[6:7], s[46:47], 0, v[146:147]
	s_add_i32 s45, s1, 0x16000
	s_mov_b32 s46, m0
	s_mov_b32 m0, s45
	s_nop 0
	global_load_lds_dwordx4 v[6:7], off
	s_mov_b32 m0, s46
	v_lshl_add_u64 v[6:7], s[50:51], 0, v[146:147]
	s_add_i32 s46, s1, 0x1e000
	s_mov_b32 s47, m0
	s_mov_b32 m0, s46
	s_nop 0
	global_load_lds_dwordx4 v[6:7], off
	s_mov_b32 m0, s47
	v_and_b32_e32 v182, 0xffffc000, v9
	v_or_b32_e32 v183, 0x800, v182
	v_or_b32_e32 v189, 0x1000, v182
	v_or_b32_e32 v199, 0x1800, v182
	v_or_b32_e32 v200, 0x2000, v182
	v_or_b32_e32 v201, 0x2800, v182
	v_or_b32_e32 v203, 0x3000, v182
	v_or_b32_e32 v206, 0x3800, v182
	s_movk_i32 s47, 0x6000
	v_and_or_b32 v7, v8, s47, v12
	ds_read_b128 v[8:11], v7 offset:32768
	v_or_b32_e32 v6, v12, v182
	ds_read_b128 v[12:15], v7 offset:34816
	ds_read_b128 v[16:19], v7 offset:36864
	ds_read_b128 v[24:27], v7 offset:38912
	ds_read_b128 v[20:23], v6
	ds_read_b128 v[28:31], v6 offset:2048
	ds_read_b128 v[32:35], v6 offset:4096
	ds_read_b128 v[36:39], v6 offset:6144
	s_waitcnt lgkmcnt(3)
	v_mfma_f32_16x16x32_bf16 v[40:43], v[8:11], v[20:23], 0
	v_mfma_f32_16x16x32_bf16 v[44:47], v[12:15], v[20:23], 0
	v_mfma_f32_16x16x32_bf16 v[48:51], v[16:19], v[20:23], 0
	v_mfma_f32_16x16x32_bf16 v[20:23], v[24:27], v[20:23], 0
	ds_read_b128 v[52:55], v6 offset:8192
	s_waitcnt lgkmcnt(3)
	v_mfma_f32_16x16x32_bf16 v[56:59], v[8:11], v[28:31], 0
	v_mfma_f32_16x16x32_bf16 v[60:63], v[12:15], v[28:31], 0
	v_mfma_f32_16x16x32_bf16 v[64:67], v[16:19], v[28:31], 0
	v_mfma_f32_16x16x32_bf16 v[28:31], v[24:27], v[28:31], 0
	ds_read_b128 v[68:71], v6 offset:10240
	s_waitcnt lgkmcnt(3)
	v_mfma_f32_16x16x32_bf16 v[72:75], v[8:11], v[32:35], 0
	v_mfma_f32_16x16x32_bf16 v[76:79], v[12:15], v[32:35], 0
	v_mfma_f32_16x16x32_bf16 v[80:83], v[16:19], v[32:35], 0
	v_mfma_f32_16x16x32_bf16 v[32:35], v[24:27], v[32:35], 0
	ds_read_b128 v[84:87], v6 offset:12288
	s_waitcnt lgkmcnt(3)
	v_mfma_f32_16x16x32_bf16 v[88:91], v[8:11], v[36:39], 0
	v_mfma_f32_16x16x32_bf16 v[92:95], v[12:15], v[36:39], 0
	v_mfma_f32_16x16x32_bf16 v[96:99], v[16:19], v[36:39], 0
	v_mfma_f32_16x16x32_bf16 v[36:39], v[24:27], v[36:39], 0
	ds_read_b128 v[100:103], v6 offset:14336
	s_waitcnt lgkmcnt(3)
	v_mfma_f32_16x16x32_bf16 v[104:107], v[8:11], v[52:55], 0
	v_mfma_f32_16x16x32_bf16 v[108:111], v[12:15], v[52:55], 0
	v_mfma_f32_16x16x32_bf16 v[112:115], v[16:19], v[52:55], 0
	v_mfma_f32_16x16x32_bf16 v[52:55], v[24:27], v[52:55], 0
	s_waitcnt lgkmcnt(2)
	v_mfma_f32_16x16x32_bf16 v[116:119], v[8:11], v[68:71], 0
	v_mfma_f32_16x16x32_bf16 v[120:123], v[12:15], v[68:71], 0
	v_mfma_f32_16x16x32_bf16 v[124:127], v[16:19], v[68:71], 0
	v_mfma_f32_16x16x32_bf16 v[68:71], v[24:27], v[68:71], 0
	s_waitcnt lgkmcnt(1)
	v_mfma_f32_16x16x32_bf16 v[128:131], v[8:11], v[84:87], 0
	v_mfma_f32_16x16x32_bf16 v[132:135], v[12:15], v[84:87], 0
	v_mfma_f32_16x16x32_bf16 v[136:139], v[16:19], v[84:87], 0
	v_mfma_f32_16x16x32_bf16 v[84:87], v[24:27], v[84:87], 0
	s_waitcnt lgkmcnt(0)
	v_mfma_f32_16x16x32_bf16 v[8:11], v[8:11], v[100:103], 0
	v_mfma_f32_16x16x32_bf16 v[12:15], v[12:15], v[100:103], 0
	v_mfma_f32_16x16x32_bf16 v[16:19], v[16:19], v[100:103], 0
	v_mfma_f32_16x16x32_bf16 v[24:27], v[24:27], v[100:103], 0
	ds_read_b128 v[100:103], v7 offset:33792
	ds_read_b128 v[140:143], v7 offset:35840
	ds_read_b128 v[150:153], v7 offset:37888
	ds_read_b128 v[158:161], v7 offset:39936
	ds_read_b128 v[154:157], v6 offset:1024
	ds_read_b128 v[162:165], v6 offset:3072
	ds_read_b128 v[166:169], v6 offset:5120
	ds_read_b128 v[170:173], v6 offset:7168
	s_waitcnt lgkmcnt(3)
	v_mfma_f32_16x16x32_bf16 v[40:43], v[100:103], v[154:157], v[40:43]
	v_mfma_f32_16x16x32_bf16 v[44:47], v[140:143], v[154:157], v[44:47]
	v_mfma_f32_16x16x32_bf16 v[48:51], v[150:153], v[154:157], v[48:51]
	v_mfma_f32_16x16x32_bf16 v[20:23], v[158:161], v[154:157], v[20:23]
	ds_read_b128 v[154:157], v6 offset:9216
	s_waitcnt lgkmcnt(3)
	v_mfma_f32_16x16x32_bf16 v[56:59], v[100:103], v[162:165], v[56:59]
	v_mfma_f32_16x16x32_bf16 v[60:63], v[140:143], v[162:165], v[60:63]
	v_mfma_f32_16x16x32_bf16 v[64:67], v[150:153], v[162:165], v[64:67]
	v_mfma_f32_16x16x32_bf16 v[28:31], v[158:161], v[162:165], v[28:31]
	ds_read_b128 v[162:165], v6 offset:11264
	s_waitcnt lgkmcnt(3)
	v_mfma_f32_16x16x32_bf16 v[72:75], v[100:103], v[166:169], v[72:75]
	v_mfma_f32_16x16x32_bf16 v[76:79], v[140:143], v[166:169], v[76:79]
	v_mfma_f32_16x16x32_bf16 v[80:83], v[150:153], v[166:169], v[80:83]
	v_mfma_f32_16x16x32_bf16 v[32:35], v[158:161], v[166:169], v[32:35]
	ds_read_b128 v[166:169], v6 offset:13312
	s_waitcnt lgkmcnt(3)
	v_mfma_f32_16x16x32_bf16 v[88:91], v[100:103], v[170:173], v[88:91]
	v_mfma_f32_16x16x32_bf16 v[92:95], v[140:143], v[170:173], v[92:95]
	v_mfma_f32_16x16x32_bf16 v[96:99], v[150:153], v[170:173], v[96:99]
	v_mfma_f32_16x16x32_bf16 v[36:39], v[158:161], v[170:173], v[36:39]
	ds_read_b128 v[170:173], v6 offset:15360
	s_waitcnt lgkmcnt(3)
	v_mfma_f32_16x16x32_bf16 v[104:107], v[100:103], v[154:157], v[104:107]
	v_mfma_f32_16x16x32_bf16 v[108:111], v[140:143], v[154:157], v[108:111]
	v_mfma_f32_16x16x32_bf16 v[112:115], v[150:153], v[154:157], v[112:115]
	v_mfma_f32_16x16x32_bf16 v[52:55], v[158:161], v[154:157], v[52:55]
	s_waitcnt lgkmcnt(2)
	v_mfma_f32_16x16x32_bf16 v[116:119], v[100:103], v[162:165], v[116:119]
	v_mfma_f32_16x16x32_bf16 v[120:123], v[140:143], v[162:165], v[120:123]
	v_mfma_f32_16x16x32_bf16 v[124:127], v[150:153], v[162:165], v[124:127]
	v_mfma_f32_16x16x32_bf16 v[68:71], v[158:161], v[162:165], v[68:71]
	s_waitcnt lgkmcnt(1)
	v_mfma_f32_16x16x32_bf16 v[128:131], v[100:103], v[166:169], v[128:131]
	v_mfma_f32_16x16x32_bf16 v[132:135], v[140:143], v[166:169], v[132:135]
	v_mfma_f32_16x16x32_bf16 v[136:139], v[150:153], v[166:169], v[136:139]
	v_mfma_f32_16x16x32_bf16 v[84:87], v[158:161], v[166:169], v[84:87]
	s_waitcnt lgkmcnt(0)
	v_mfma_f32_16x16x32_bf16 v[100:103], v[100:103], v[170:173], v[8:11]
	v_mfma_f32_16x16x32_bf16 v[150:153], v[150:153], v[170:173], v[16:19]
	v_mfma_f32_16x16x32_bf16 v[24:27], v[158:161], v[170:173], v[24:27]
	v_mfma_f32_16x16x32_bf16 v[140:143], v[140:143], v[170:173], v[12:15]
	s_add_u32 s50, s14, 0x100
	s_addc_u32 s51, s15, 0
	s_add_u32 s52, s20, 0x100
	s_waitcnt vmcnt(0)
	s_barrier
	s_addc_u32 s53, s21, 0
	v_lshl_add_u64 v[8:9], s[50:51], 0, v[0:1]
	s_mov_b32 s47, m0
	s_mov_b32 m0, s1
	s_nop 0
	global_load_lds_dwordx4 v[8:9], off
	s_mov_b32 m0, s47
	v_lshl_add_u64 v[8:9], s[52:53], 0, v[0:1]
	s_mov_b32 s47, m0
	s_mov_b32 m0, s34
	s_nop 0
	global_load_lds_dwordx4 v[8:9], off
	s_mov_b32 m0, s47
	v_lshl_add_u64 v[8:9], s[50:51], 0, v[2:3]
	s_mov_b32 s47, m0
	s_mov_b32 m0, s35
	s_nop 0
	global_load_lds_dwordx4 v[8:9], off
	s_mov_b32 m0, s47
	v_lshl_add_u64 v[8:9], s[52:53], 0, v[2:3]
	s_mov_b32 s47, m0
	s_mov_b32 m0, s36
	s_nop 0
	global_load_lds_dwordx4 v[8:9], off
	s_mov_b32 m0, s47
	v_lshl_add_u64 v[8:9], s[50:51], 0, v[4:5]
	s_mov_b32 s47, m0
	s_mov_b32 m0, s37
	s_nop 0
	global_load_lds_dwordx4 v[8:9], off
	s_mov_b32 m0, s47
	v_lshl_add_u64 v[8:9], s[52:53], 0, v[4:5]
	s_mov_b32 s47, m0
	s_mov_b32 m0, s38
	s_nop 0
	global_load_lds_dwordx4 v[8:9], off
	s_mov_b32 m0, s47
	v_lshl_add_u64 v[8:9], s[50:51], 0, v[146:147]
	s_mov_b32 s47, m0
	s_mov_b32 m0, s39
	s_nop 0
	global_load_lds_dwordx4 v[8:9], off
	s_mov_b32 m0, s47
	v_lshl_add_u64 v[8:9], s[52:53], 0, v[146:147]
	s_mov_b32 s47, m0
	s_mov_b32 m0, s40
	s_nop 0
	global_load_lds_dwordx4 v[8:9], off
	s_mov_b32 m0, s47
	v_or_b32_e32 v8, 0x18000, v7
	v_or_b32_e32 v9, 0x18800, v7
	v_or_b32_e32 v11, 0x19000, v7
	v_or_b32_e32 v10, 0x19800, v7
	ds_read_b128 v[154:157], v8
	ds_read_b128 v[158:161], v9
	ds_read_b128 v[162:165], v11
	ds_read_b128 v[166:169], v10
	v_bitop3_b32 v207, v145, s33, v149 bitop3:0xde
	v_add_u32_e32 v12, v207, v182
	ds_read_b128 v[16:19], v12
	v_add_u32_e32 v13, v207, v183
	v_add_u32_e32 v14, v207, v189
	v_add_u32_e32 v15, v207, v199
	ds_read_b128 v[170:173], v13
	ds_read_b128 v[174:177], v14
	ds_read_b128 v[178:181], v15
	s_waitcnt lgkmcnt(3)
	v_mfma_f32_16x16x32_bf16 v[40:43], v[154:157], v[16:19], v[40:43]
	v_mfma_f32_16x16x32_bf16 v[44:47], v[158:161], v[16:19], v[44:47]
	v_mfma_f32_16x16x32_bf16 v[48:51], v[162:165], v[16:19], v[48:51]
	v_mfma_f32_16x16x32_bf16 v[214:217], v[166:169], v[16:19], v[20:23]
	v_add_u32_e32 v16, v207, v200
	v_add_u32_e32 v17, v207, v201
	v_add_u32_e32 v18, v207, v203
	v_add_u32_e32 v19, v207, v206
	ds_read_b128 v[20:23], v16
	s_waitcnt lgkmcnt(3)
	v_mfma_f32_16x16x32_bf16 v[56:59], v[154:157], v[170:173], v[56:59]
	v_mfma_f32_16x16x32_bf16 v[60:63], v[158:161], v[170:173], v[60:63]
	v_mfma_f32_16x16x32_bf16 v[64:67], v[162:165], v[170:173], v[64:67]
	v_mfma_f32_16x16x32_bf16 v[170:173], v[166:169], v[170:173], v[28:31]
	s_nop 2
	ds_read_b128 v[28:31], v17
	s_waitcnt lgkmcnt(3)
	v_mfma_f32_16x16x32_bf16 v[72:75], v[154:157], v[174:177], v[72:75]
	v_mfma_f32_16x16x32_bf16 v[76:79], v[158:161], v[174:177], v[76:79]
	v_mfma_f32_16x16x32_bf16 v[80:83], v[162:165], v[174:177], v[80:83]
	v_mfma_f32_16x16x32_bf16 v[32:35], v[166:169], v[174:177], v[32:35]
	ds_read_b128 v[174:177], v18
	s_waitcnt lgkmcnt(3)
	v_mfma_f32_16x16x32_bf16 v[88:91], v[154:157], v[178:181], v[88:91]
	v_mfma_f32_16x16x32_bf16 v[92:95], v[158:161], v[178:181], v[92:95]
	v_mfma_f32_16x16x32_bf16 v[96:99], v[162:165], v[178:181], v[96:99]
	v_mfma_f32_16x16x32_bf16 v[36:39], v[166:169], v[178:181], v[36:39]
	ds_read_b128 v[178:181], v19
	s_waitcnt lgkmcnt(3)
	v_mfma_f32_16x16x32_bf16 v[104:107], v[154:157], v[20:23], v[104:107]
	v_mfma_f32_16x16x32_bf16 v[108:111], v[158:161], v[20:23], v[108:111]
	v_mfma_f32_16x16x32_bf16 v[112:115], v[162:165], v[20:23], v[112:115]
	v_mfma_f32_16x16x32_bf16 v[52:55], v[166:169], v[20:23], v[52:55]
	s_waitcnt lgkmcnt(2)
	v_mfma_f32_16x16x32_bf16 v[116:119], v[154:157], v[28:31], v[116:119]
	v_mfma_f32_16x16x32_bf16 v[120:123], v[158:161], v[28:31], v[120:123]
	v_mfma_f32_16x16x32_bf16 v[124:127], v[162:165], v[28:31], v[124:127]
	v_mfma_f32_16x16x32_bf16 v[68:71], v[166:169], v[28:31], v[68:71]
	s_waitcnt lgkmcnt(1)
	v_mfma_f32_16x16x32_bf16 v[128:131], v[154:157], v[174:177], v[128:131]
	v_mfma_f32_16x16x32_bf16 v[132:135], v[158:161], v[174:177], v[132:135]
	v_mfma_f32_16x16x32_bf16 v[84:87], v[166:169], v[174:177], v[84:87]
	s_waitcnt lgkmcnt(0)
	v_mfma_f32_16x16x32_bf16 v[100:103], v[154:157], v[178:181], v[100:103]
	v_mfma_f32_16x16x32_bf16 v[150:153], v[162:165], v[178:181], v[150:153]
	v_mfma_f32_16x16x32_bf16 v[154:157], v[166:169], v[178:181], v[24:27]
	v_mfma_f32_16x16x32_bf16 v[136:139], v[162:165], v[174:177], v[136:139]
	v_mfma_f32_16x16x32_bf16 v[140:143], v[158:161], v[178:181], v[140:143]
	v_or_b32_e32 v20, 0x18400, v7
	v_or_b32_e32 v21, 0x18c00, v7
	v_or_b32_e32 v23, 0x19400, v7
	v_or_b32_e32 v22, 0x19c00, v7
	ds_read_b128 v[158:161], v20
	ds_read_b128 v[162:165], v21
	ds_read_b128 v[166:169], v23
	ds_read_b128 v[174:177], v22
	s_mov_b32 s47, 0x10400
	v_bitop3_b32 v145, v145, s47, v149 bitop3:0xde
	v_add_u32_e32 v24, v145, v182
	ds_read_b128 v[28:31], v24
	v_add_u32_e32 v25, v145, v183
	v_add_u32_e32 v26, v145, v189
	v_add_u32_e32 v27, v145, v199
	ds_read_b128 v[178:181], v25
	ds_read_b128 v[218:221], v26
	ds_read_b128 v[222:225], v27
	s_waitcnt lgkmcnt(3)
	v_mfma_f32_16x16x32_bf16 v[40:43], v[158:161], v[28:31], v[40:43]
	v_mfma_f32_16x16x32_bf16 v[44:47], v[162:165], v[28:31], v[44:47]
	v_mfma_f32_16x16x32_bf16 v[48:51], v[166:169], v[28:31], v[48:51]
	v_mfma_f32_16x16x32_bf16 v[214:217], v[174:177], v[28:31], v[214:217]
	v_add_u32_e32 v28, v145, v200
	v_add_u32_e32 v29, v145, v201
	v_add_u32_e32 v30, v145, v203
	v_add_u32_e32 v31, v145, v206
	ds_read_b128 v[226:229], v28
	s_waitcnt lgkmcnt(3)
	v_mfma_f32_16x16x32_bf16 v[56:59], v[158:161], v[178:181], v[56:59]
	v_mfma_f32_16x16x32_bf16 v[60:63], v[162:165], v[178:181], v[60:63]
	v_mfma_f32_16x16x32_bf16 v[64:67], v[166:169], v[178:181], v[64:67]
	v_mfma_f32_16x16x32_bf16 v[170:173], v[174:177], v[178:181], v[170:173]
	ds_read_b128 v[178:181], v29
	s_waitcnt lgkmcnt(3)
	v_mfma_f32_16x16x32_bf16 v[72:75], v[158:161], v[218:221], v[72:75]
	v_mfma_f32_16x16x32_bf16 v[76:79], v[162:165], v[218:221], v[76:79]
	v_mfma_f32_16x16x32_bf16 v[80:83], v[166:169], v[218:221], v[80:83]
	v_mfma_f32_16x16x32_bf16 v[32:35], v[174:177], v[218:221], v[32:35]
	ds_read_b128 v[218:221], v30
	s_waitcnt lgkmcnt(3)
	v_mfma_f32_16x16x32_bf16 v[88:91], v[158:161], v[222:225], v[88:91]
	v_mfma_f32_16x16x32_bf16 v[92:95], v[162:165], v[222:225], v[92:95]
	v_mfma_f32_16x16x32_bf16 v[96:99], v[166:169], v[222:225], v[96:99]
	v_mfma_f32_16x16x32_bf16 v[36:39], v[174:177], v[222:225], v[36:39]
	ds_read_b128 v[222:225], v31
	s_waitcnt lgkmcnt(3)
	v_mfma_f32_16x16x32_bf16 v[104:107], v[158:161], v[226:229], v[104:107]
	v_mfma_f32_16x16x32_bf16 v[108:111], v[162:165], v[226:229], v[108:111]
	v_mfma_f32_16x16x32_bf16 v[112:115], v[166:169], v[226:229], v[112:115]
	v_mfma_f32_16x16x32_bf16 v[52:55], v[174:177], v[226:229], v[52:55]
	s_waitcnt lgkmcnt(2)
	v_mfma_f32_16x16x32_bf16 v[116:119], v[158:161], v[178:181], v[116:119]
	v_mfma_f32_16x16x32_bf16 v[120:123], v[162:165], v[178:181], v[120:123]
	v_mfma_f32_16x16x32_bf16 v[124:127], v[166:169], v[178:181], v[124:127]
	v_mfma_f32_16x16x32_bf16 v[68:71], v[174:177], v[178:181], v[68:71]
	s_waitcnt lgkmcnt(1)
	v_mfma_f32_16x16x32_bf16 v[132:135], v[162:165], v[218:221], v[132:135]
	v_mfma_f32_16x16x32_bf16 v[84:87], v[174:177], v[218:221], v[84:87]
	s_waitcnt lgkmcnt(0)
	v_mfma_f32_16x16x32_bf16 v[100:103], v[158:161], v[222:225], v[100:103]
	v_mfma_f32_16x16x32_bf16 v[150:153], v[166:169], v[222:225], v[150:153]
	v_mfma_f32_16x16x32_bf16 v[154:157], v[174:177], v[222:225], v[154:157]
	v_mfma_f32_16x16x32_bf16 v[128:131], v[158:161], v[218:221], v[128:131]
	v_mfma_f32_16x16x32_bf16 v[136:139], v[166:169], v[218:221], v[136:139]
	v_mfma_f32_16x16x32_bf16 v[140:143], v[162:165], v[222:225], v[140:143]
	s_add_u32 s50, s14, 0x180
	s_addc_u32 s51, s15, 0
	s_add_u32 s52, s20, 0x180
	s_waitcnt vmcnt(0)
	s_barrier
	s_addc_u32 s53, s21, 0
	v_lshl_add_u64 v[158:159], s[50:51], 0, v[0:1]
	s_mov_b32 s47, m0
	s_mov_b32 m0, s27
	s_nop 0
	global_load_lds_dwordx4 v[158:159], off
	s_mov_b32 m0, s47
	v_lshl_add_u64 v[158:159], s[52:53], 0, v[0:1]
	s_mov_b32 s47, m0
	s_mov_b32 m0, s26
	s_nop 0
	global_load_lds_dwordx4 v[158:159], off
	s_mov_b32 m0, s47
	v_lshl_add_u64 v[158:159], s[50:51], 0, v[2:3]
	s_mov_b32 s47, m0
	s_mov_b32 m0, s41
	s_nop 0
	global_load_lds_dwordx4 v[158:159], off
	s_mov_b32 m0, s47
	v_lshl_add_u64 v[158:159], s[52:53], 0, v[2:3]
	s_mov_b32 s47, m0
	s_mov_b32 m0, s42
	s_nop 0
	global_load_lds_dwordx4 v[158:159], off
	s_mov_b32 m0, s47
	v_lshl_add_u64 v[158:159], s[50:51], 0, v[4:5]
	s_mov_b32 s47, m0
	s_mov_b32 m0, s43
	s_nop 0
	global_load_lds_dwordx4 v[158:159], off
	s_mov_b32 m0, s47
	v_lshl_add_u64 v[158:159], s[52:53], 0, v[4:5]
	s_mov_b32 s47, m0
	s_mov_b32 m0, s44
	s_nop 0
	global_load_lds_dwordx4 v[158:159], off
	s_mov_b32 m0, s47
	v_lshl_add_u64 v[158:159], s[50:51], 0, v[146:147]
	s_mov_b32 s47, m0
	s_mov_b32 m0, s45
	s_nop 0
	global_load_lds_dwordx4 v[158:159], off
	s_mov_b32 m0, s47
	v_lshl_add_u64 v[158:159], s[52:53], 0, v[146:147]
	s_mov_b32 s47, m0
	s_mov_b32 m0, s46
	s_nop 0
	global_load_lds_dwordx4 v[158:159], off
	s_mov_b32 m0, s47
	ds_read_b128 v[158:161], v7 offset:32768
	ds_read_b128 v[162:165], v7 offset:34816
	ds_read_b128 v[166:169], v7 offset:36864
	ds_read_b128 v[178:181], v7 offset:38912
	ds_read_b128 v[174:177], v6
	ds_read_b128 v[218:221], v6 offset:2048
	ds_read_b128 v[222:225], v6 offset:4096
	ds_read_b128 v[226:229], v6 offset:6144
	s_waitcnt lgkmcnt(3)
	v_mfma_f32_16x16x32_bf16 v[40:43], v[158:161], v[174:177], v[40:43]
	v_mfma_f32_16x16x32_bf16 v[44:47], v[162:165], v[174:177], v[44:47]
	v_mfma_f32_16x16x32_bf16 v[48:51], v[166:169], v[174:177], v[48:51]
	v_mfma_f32_16x16x32_bf16 v[174:177], v[178:181], v[174:177], v[214:217]
	s_nop 2
	ds_read_b128 v[214:217], v6 offset:8192
	s_waitcnt lgkmcnt(3)
	v_mfma_f32_16x16x32_bf16 v[56:59], v[158:161], v[218:221], v[56:59]
	v_mfma_f32_16x16x32_bf16 v[60:63], v[162:165], v[218:221], v[60:63]
	v_mfma_f32_16x16x32_bf16 v[64:67], v[166:169], v[218:221], v[64:67]
	v_mfma_f32_16x16x32_bf16 v[170:173], v[178:181], v[218:221], v[170:173]
	ds_read_b128 v[218:221], v6 offset:10240
	s_waitcnt lgkmcnt(3)
	v_mfma_f32_16x16x32_bf16 v[72:75], v[158:161], v[222:225], v[72:75]
	v_mfma_f32_16x16x32_bf16 v[76:79], v[162:165], v[222:225], v[76:79]
	v_mfma_f32_16x16x32_bf16 v[80:83], v[166:169], v[222:225], v[80:83]
	v_mfma_f32_16x16x32_bf16 v[32:35], v[178:181], v[222:225], v[32:35]
	ds_read_b128 v[222:225], v6 offset:12288
	s_waitcnt lgkmcnt(3)
	v_mfma_f32_16x16x32_bf16 v[88:91], v[158:161], v[226:229], v[88:91]
	v_mfma_f32_16x16x32_bf16 v[92:95], v[162:165], v[226:229], v[92:95]
	v_mfma_f32_16x16x32_bf16 v[96:99], v[166:169], v[226:229], v[96:99]
	v_mfma_f32_16x16x32_bf16 v[36:39], v[178:181], v[226:229], v[36:39]
	ds_read_b128 v[226:229], v6 offset:14336
	s_waitcnt lgkmcnt(3)
	v_mfma_f32_16x16x32_bf16 v[104:107], v[158:161], v[214:217], v[104:107]
	v_mfma_f32_16x16x32_bf16 v[108:111], v[162:165], v[214:217], v[108:111]
	v_mfma_f32_16x16x32_bf16 v[112:115], v[166:169], v[214:217], v[112:115]
	v_mfma_f32_16x16x32_bf16 v[52:55], v[178:181], v[214:217], v[52:55]
	s_waitcnt lgkmcnt(2)
	v_mfma_f32_16x16x32_bf16 v[116:119], v[158:161], v[218:221], v[116:119]
	v_mfma_f32_16x16x32_bf16 v[120:123], v[162:165], v[218:221], v[120:123]
	v_mfma_f32_16x16x32_bf16 v[124:127], v[166:169], v[218:221], v[124:127]
	v_mfma_f32_16x16x32_bf16 v[68:71], v[178:181], v[218:221], v[68:71]
	s_waitcnt lgkmcnt(1)
	v_mfma_f32_16x16x32_bf16 v[132:135], v[162:165], v[222:225], v[132:135]
	v_mfma_f32_16x16x32_bf16 v[84:87], v[178:181], v[222:225], v[84:87]
	s_waitcnt lgkmcnt(0)
	v_mfma_f32_16x16x32_bf16 v[100:103], v[158:161], v[226:229], v[100:103]
	v_mfma_f32_16x16x32_bf16 v[150:153], v[166:169], v[226:229], v[150:153]
	v_mfma_f32_16x16x32_bf16 v[154:157], v[178:181], v[226:229], v[154:157]
	v_mfma_f32_16x16x32_bf16 v[128:131], v[158:161], v[222:225], v[128:131]
	v_mfma_f32_16x16x32_bf16 v[136:139], v[166:169], v[222:225], v[136:139]
	v_mfma_f32_16x16x32_bf16 v[140:143], v[162:165], v[226:229], v[140:143]
	ds_read_b128 v[158:161], v7 offset:33792
	ds_read_b128 v[162:165], v7 offset:35840
	ds_read_b128 v[166:169], v7 offset:37888
	ds_read_b128 v[214:217], v7 offset:39936
	ds_read_b128 v[178:181], v6 offset:1024
	ds_read_b128 v[218:221], v6 offset:3072
	ds_read_b128 v[222:225], v6 offset:5120
	ds_read_b128 v[226:229], v6 offset:7168
	s_waitcnt lgkmcnt(3)
	v_mfma_f32_16x16x32_bf16 v[40:43], v[158:161], v[178:181], v[40:43]
	v_mfma_f32_16x16x32_bf16 v[44:47], v[162:165], v[178:181], v[44:47]
	v_mfma_f32_16x16x32_bf16 v[48:51], v[166:169], v[178:181], v[48:51]
	v_mfma_f32_16x16x32_bf16 v[174:177], v[214:217], v[178:181], v[174:177]
	ds_read_b128 v[178:181], v6 offset:9216
	s_waitcnt lgkmcnt(3)
	v_mfma_f32_16x16x32_bf16 v[56:59], v[158:161], v[218:221], v[56:59]
	v_mfma_f32_16x16x32_bf16 v[60:63], v[162:165], v[218:221], v[60:63]
	v_mfma_f32_16x16x32_bf16 v[64:67], v[166:169], v[218:221], v[64:67]
	v_mfma_f32_16x16x32_bf16 v[170:173], v[214:217], v[218:221], v[170:173]
	ds_read_b128 v[218:221], v6 offset:11264
	s_waitcnt lgkmcnt(3)
	v_mfma_f32_16x16x32_bf16 v[72:75], v[158:161], v[222:225], v[72:75]
	v_mfma_f32_16x16x32_bf16 v[76:79], v[162:165], v[222:225], v[76:79]
	v_mfma_f32_16x16x32_bf16 v[80:83], v[166:169], v[222:225], v[80:83]
	v_mfma_f32_16x16x32_bf16 v[32:35], v[214:217], v[222:225], v[32:35]
	ds_read_b128 v[222:225], v6 offset:13312
	s_waitcnt lgkmcnt(3)
	v_mfma_f32_16x16x32_bf16 v[88:91], v[158:161], v[226:229], v[88:91]
	v_mfma_f32_16x16x32_bf16 v[92:95], v[162:165], v[226:229], v[92:95]
	v_mfma_f32_16x16x32_bf16 v[96:99], v[166:169], v[226:229], v[96:99]
	v_mfma_f32_16x16x32_bf16 v[36:39], v[214:217], v[226:229], v[36:39]
	ds_read_b128 v[226:229], v6 offset:15360
	s_waitcnt lgkmcnt(3)
	v_mfma_f32_16x16x32_bf16 v[104:107], v[158:161], v[178:181], v[104:107]
	v_mfma_f32_16x16x32_bf16 v[108:111], v[162:165], v[178:181], v[108:111]
	v_mfma_f32_16x16x32_bf16 v[112:115], v[166:169], v[178:181], v[112:115]
	v_mfma_f32_16x16x32_bf16 v[52:55], v[214:217], v[178:181], v[52:55]
	s_waitcnt lgkmcnt(2)
	v_mfma_f32_16x16x32_bf16 v[116:119], v[158:161], v[218:221], v[116:119]
	v_mfma_f32_16x16x32_bf16 v[120:123], v[162:165], v[218:221], v[120:123]
	v_mfma_f32_16x16x32_bf16 v[124:127], v[166:169], v[218:221], v[124:127]
	v_mfma_f32_16x16x32_bf16 v[68:71], v[214:217], v[218:221], v[68:71]
	s_waitcnt lgkmcnt(1)
	v_mfma_f32_16x16x32_bf16 v[132:135], v[162:165], v[222:225], v[132:135]
	v_mfma_f32_16x16x32_bf16 v[84:87], v[214:217], v[222:225], v[84:87]
	s_waitcnt lgkmcnt(0)
	v_mfma_f32_16x16x32_bf16 v[100:103], v[158:161], v[226:229], v[100:103]
	v_mfma_f32_16x16x32_bf16 v[150:153], v[166:169], v[226:229], v[150:153]
	v_mfma_f32_16x16x32_bf16 v[154:157], v[214:217], v[226:229], v[154:157]
	v_mfma_f32_16x16x32_bf16 v[128:131], v[158:161], v[222:225], v[128:131]
	v_mfma_f32_16x16x32_bf16 v[136:139], v[166:169], v[222:225], v[136:139]
	v_mfma_f32_16x16x32_bf16 v[140:143], v[162:165], v[226:229], v[140:143]
	s_add_u32 s50, s14, 0x200
	s_addc_u32 s51, s15, 0
	s_add_u32 s52, s20, 0x200
	s_waitcnt vmcnt(0)
	s_barrier
	s_addc_u32 s53, s21, 0
	ds_read_b128 v[158:161], v8
	ds_read_b128 v[162:165], v12
	ds_read_b128 v[166:169], v9
	ds_read_b128 v[178:181], v13
	ds_read_b128 v[214:217], v11
	ds_read_b128 v[218:221], v10
	ds_read_b128 v[222:225], v14
	ds_read_b128 v[226:229], v15
	s_waitcnt lgkmcnt(6)
	v_mfma_f32_16x16x32_bf16 v[40:43], v[158:161], v[162:165], v[40:43]
	s_waitcnt lgkmcnt(5)
	v_mfma_f32_16x16x32_bf16 v[44:47], v[166:169], v[162:165], v[44:47]
	s_waitcnt lgkmcnt(4)
	v_mfma_f32_16x16x32_bf16 v[56:59], v[158:161], v[178:181], v[56:59]
	s_mov_b32 m0, s1
	v_mfma_f32_16x16x32_bf16 v[60:63], v[166:169], v[178:181], v[60:63]
	global_load_lds_dwordx4 v0, s[50:51]
	s_waitcnt lgkmcnt(3)
	v_mfma_f32_16x16x32_bf16 v[48:51], v[214:217], v[162:165], v[48:51]
	v_mfma_f32_16x16x32_bf16 v[64:67], v[214:217], v[178:181], v[64:67]
	s_waitcnt lgkmcnt(2)
	v_mfma_f32_16x16x32_bf16 v[174:177], v[218:221], v[162:165], v[174:177]
	ds_read_b128 v[162:165], v16
	v_mfma_f32_16x16x32_bf16 v[170:173], v[218:221], v[178:181], v[170:173]
	ds_read_b128 v[178:181], v17
	s_waitcnt lgkmcnt(3)
	s_mov_b32 m0, s34
	v_mfma_f32_16x16x32_bf16 v[72:75], v[158:161], v[222:225], v[72:75]
	global_load_lds_dwordx4 v0, s[52:53]
	v_mfma_f32_16x16x32_bf16 v[76:79], v[166:169], v[222:225], v[76:79]
	v_mfma_f32_16x16x32_bf16 v[80:83], v[214:217], v[222:225], v[80:83]
	v_mfma_f32_16x16x32_bf16 v[32:35], v[218:221], v[222:225], v[32:35]
	ds_read_b128 v[222:225], v18
	s_waitcnt lgkmcnt(3)
	v_mfma_f32_16x16x32_bf16 v[88:91], v[158:161], v[226:229], v[88:91]
	s_mov_b32 m0, s35
	v_mfma_f32_16x16x32_bf16 v[92:95], v[166:169], v[226:229], v[92:95]
	global_load_lds_dwordx4 v2, s[50:51]
	v_mfma_f32_16x16x32_bf16 v[96:99], v[214:217], v[226:229], v[96:99]
	v_mfma_f32_16x16x32_bf16 v[36:39], v[218:221], v[226:229], v[36:39]
	ds_read_b128 v[226:229], v19
	s_waitcnt lgkmcnt(3)
	v_mfma_f32_16x16x32_bf16 v[104:107], v[158:161], v[162:165], v[104:107]
	s_waitcnt lgkmcnt(2)
	v_mfma_f32_16x16x32_bf16 v[116:119], v[158:161], v[178:181], v[116:119]
	s_waitcnt lgkmcnt(1)
	s_mov_b32 m0, s36
	v_mfma_f32_16x16x32_bf16 v[128:131], v[158:161], v[222:225], v[128:131]
	global_load_lds_dwordx4 v2, s[52:53]
	s_waitcnt lgkmcnt(0)
	v_mfma_f32_16x16x32_bf16 v[100:103], v[158:161], v[226:229], v[100:103]
	ds_read_b128 v[158:161], v20
	v_mfma_f32_16x16x32_bf16 v[108:111], v[166:169], v[162:165], v[108:111]
	v_mfma_f32_16x16x32_bf16 v[120:123], v[166:169], v[178:181], v[120:123]
	v_mfma_f32_16x16x32_bf16 v[132:135], v[166:169], v[222:225], v[132:135]
	s_mov_b32 m0, s37
	v_mfma_f32_16x16x32_bf16 v[140:143], v[166:169], v[226:229], v[140:143]
	global_load_lds_dwordx4 v4, s[50:51]
	ds_read_b128 v[166:169], v24
	v_mfma_f32_16x16x32_bf16 v[112:115], v[214:217], v[162:165], v[112:115]
	v_mfma_f32_16x16x32_bf16 v[52:55], v[218:221], v[162:165], v[52:55]
	ds_read_b128 v[162:165], v21
	v_mfma_f32_16x16x32_bf16 v[124:127], v[214:217], v[178:181], v[124:127]
	v_mfma_f32_16x16x32_bf16 v[68:71], v[218:221], v[178:181], v[68:71]
	ds_read_b128 v[178:181], v25
	s_mov_b32 m0, s38
	v_mfma_f32_16x16x32_bf16 v[136:139], v[214:217], v[222:225], v[136:139]
	global_load_lds_dwordx4 v4, s[52:53]
	v_mfma_f32_16x16x32_bf16 v[84:87], v[218:221], v[222:225], v[84:87]
	ds_read_b128 v[222:225], v26
	v_mfma_f32_16x16x32_bf16 v[150:153], v[214:217], v[226:229], v[150:153]
	ds_read_b128 v[214:217], v23
	v_mfma_f32_16x16x32_bf16 v[154:157], v[218:221], v[226:229], v[154:157]
	ds_read_b128 v[218:221], v22
	ds_read_b128 v[226:229], v27
	s_waitcnt lgkmcnt(6)
	v_mfma_f32_16x16x32_bf16 v[40:43], v[158:161], v[166:169], v[40:43]
	s_waitcnt lgkmcnt(5)
	s_mov_b32 m0, s39
	v_mfma_f32_16x16x32_bf16 v[44:47], v[162:165], v[166:169], v[44:47]
	global_load_lds_dwordx4 v146, s[50:51]
	s_waitcnt lgkmcnt(4)
	v_mfma_f32_16x16x32_bf16 v[56:59], v[158:161], v[178:181], v[56:59]
	v_mfma_f32_16x16x32_bf16 v[60:63], v[162:165], v[178:181], v[60:63]
	s_waitcnt lgkmcnt(3)
	v_mfma_f32_16x16x32_bf16 v[72:75], v[158:161], v[222:225], v[72:75]
	v_mfma_f32_16x16x32_bf16 v[76:79], v[162:165], v[222:225], v[76:79]
	s_waitcnt lgkmcnt(2)
	s_mov_b32 m0, s40
	v_mfma_f32_16x16x32_bf16 v[48:51], v[214:217], v[166:169], v[48:51]
	global_load_lds_dwordx4 v146, s[52:53]
	s_waitcnt lgkmcnt(1)
	v_mfma_f32_16x16x32_bf16 v[174:177], v[218:221], v[166:169], v[174:177]
	ds_read_b128 v[166:169], v28
	v_mfma_f32_16x16x32_bf16 v[64:67], v[214:217], v[178:181], v[64:67]
	v_mfma_f32_16x16x32_bf16 v[170:173], v[218:221], v[178:181], v[170:173]
	ds_read_b128 v[178:181], v29
	v_mfma_f32_16x16x32_bf16 v[80:83], v[214:217], v[222:225], v[80:83]
	v_mfma_f32_16x16x32_bf16 v[32:35], v[218:221], v[222:225], v[32:35]
	ds_read_b128 v[222:225], v30
	s_waitcnt lgkmcnt(3)
	v_mfma_f32_16x16x32_bf16 v[88:91], v[158:161], v[226:229], v[88:91]
	v_mfma_f32_16x16x32_bf16 v[92:95], v[162:165], v[226:229], v[92:95]
	v_mfma_f32_16x16x32_bf16 v[96:99], v[214:217], v[226:229], v[96:99]
	v_mfma_f32_16x16x32_bf16 v[36:39], v[218:221], v[226:229], v[36:39]
	ds_read_b128 v[226:229], v31
	s_waitcnt lgkmcnt(3)
	v_mfma_f32_16x16x32_bf16 v[104:107], v[158:161], v[166:169], v[104:107]
	v_mfma_f32_16x16x32_bf16 v[108:111], v[162:165], v[166:169], v[108:111]
	v_mfma_f32_16x16x32_bf16 v[112:115], v[214:217], v[166:169], v[112:115]
	v_mfma_f32_16x16x32_bf16 v[52:55], v[218:221], v[166:169], v[52:55]
	s_waitcnt lgkmcnt(2)
	v_mfma_f32_16x16x32_bf16 v[116:119], v[158:161], v[178:181], v[116:119]
	v_mfma_f32_16x16x32_bf16 v[120:123], v[162:165], v[178:181], v[120:123]
	v_mfma_f32_16x16x32_bf16 v[124:127], v[214:217], v[178:181], v[124:127]
	v_mfma_f32_16x16x32_bf16 v[68:71], v[218:221], v[178:181], v[68:71]
	s_waitcnt lgkmcnt(1)
	v_mfma_f32_16x16x32_bf16 v[128:131], v[158:161], v[222:225], v[128:131]
	v_mfma_f32_16x16x32_bf16 v[132:135], v[162:165], v[222:225], v[132:135]
	v_mfma_f32_16x16x32_bf16 v[136:139], v[214:217], v[222:225], v[136:139]
	v_mfma_f32_16x16x32_bf16 v[84:87], v[218:221], v[222:225], v[84:87]
	s_waitcnt lgkmcnt(0)
	v_mfma_f32_16x16x32_bf16 v[100:103], v[158:161], v[226:229], v[100:103]
	v_mfma_f32_16x16x32_bf16 v[140:143], v[162:165], v[226:229], v[140:143]
	v_mfma_f32_16x16x32_bf16 v[150:153], v[214:217], v[226:229], v[150:153]
	v_mfma_f32_16x16x32_bf16 v[154:157], v[218:221], v[226:229], v[154:157]
	s_add_u32 s50, s14, 0x280
	s_addc_u32 s51, s15, 0
	s_add_u32 s52, s20, 0x280
	s_waitcnt vmcnt(0)
	s_barrier
	s_addc_u32 s53, s21, 0
	ds_read_b128 v[158:161], v7 offset:32768
	ds_read_b128 v[162:165], v6
	ds_read_b128 v[166:169], v7 offset:34816
	ds_read_b128 v[178:181], v6 offset:2048
	ds_read_b128 v[214:217], v7 offset:36864
	ds_read_b128 v[218:221], v7 offset:38912
	ds_read_b128 v[222:225], v6 offset:4096
	ds_read_b128 v[226:229], v6 offset:6144
	s_waitcnt lgkmcnt(6)
	v_mfma_f32_16x16x32_bf16 v[40:43], v[158:161], v[162:165], v[40:43]
	s_waitcnt lgkmcnt(5)
	v_mfma_f32_16x16x32_bf16 v[44:47], v[166:169], v[162:165], v[44:47]
	s_waitcnt lgkmcnt(4)
	v_mfma_f32_16x16x32_bf16 v[56:59], v[158:161], v[178:181], v[56:59]
	s_mov_b32 m0, s27
	v_mfma_f32_16x16x32_bf16 v[60:63], v[166:169], v[178:181], v[60:63]
	global_load_lds_dwordx4 v0, s[50:51]
	s_waitcnt lgkmcnt(3)
	v_mfma_f32_16x16x32_bf16 v[48:51], v[214:217], v[162:165], v[48:51]
	v_mfma_f32_16x16x32_bf16 v[64:67], v[214:217], v[178:181], v[64:67]
	s_waitcnt lgkmcnt(2)
	v_mfma_f32_16x16x32_bf16 v[174:177], v[218:221], v[162:165], v[174:177]
	ds_read_b128 v[162:165], v6 offset:8192
	v_mfma_f32_16x16x32_bf16 v[170:173], v[218:221], v[178:181], v[170:173]
	ds_read_b128 v[178:181], v6 offset:10240
	s_waitcnt lgkmcnt(3)
	s_mov_b32 m0, s26
	v_mfma_f32_16x16x32_bf16 v[72:75], v[158:161], v[222:225], v[72:75]
	global_load_lds_dwordx4 v0, s[52:53]
	v_mfma_f32_16x16x32_bf16 v[76:79], v[166:169], v[222:225], v[76:79]
	v_mfma_f32_16x16x32_bf16 v[80:83], v[214:217], v[222:225], v[80:83]
	v_mfma_f32_16x16x32_bf16 v[32:35], v[218:221], v[222:225], v[32:35]
	ds_read_b128 v[222:225], v6 offset:12288
	s_waitcnt lgkmcnt(3)
	v_mfma_f32_16x16x32_bf16 v[88:91], v[158:161], v[226:229], v[88:91]
	s_mov_b32 m0, s41
	v_mfma_f32_16x16x32_bf16 v[92:95], v[166:169], v[226:229], v[92:95]
	global_load_lds_dwordx4 v2, s[50:51]
	v_mfma_f32_16x16x32_bf16 v[96:99], v[214:217], v[226:229], v[96:99]
	v_mfma_f32_16x16x32_bf16 v[36:39], v[218:221], v[226:229], v[36:39]
	ds_read_b128 v[226:229], v6 offset:14336
	s_waitcnt lgkmcnt(3)
	v_mfma_f32_16x16x32_bf16 v[104:107], v[158:161], v[162:165], v[104:107]
	s_waitcnt lgkmcnt(2)
	v_mfma_f32_16x16x32_bf16 v[116:119], v[158:161], v[178:181], v[116:119]
	s_waitcnt lgkmcnt(1)
	s_mov_b32 m0, s42
	v_mfma_f32_16x16x32_bf16 v[128:131], v[158:161], v[222:225], v[128:131]
	global_load_lds_dwordx4 v2, s[52:53]
	s_waitcnt lgkmcnt(0)
	v_mfma_f32_16x16x32_bf16 v[100:103], v[158:161], v[226:229], v[100:103]
	ds_read_b128 v[158:161], v7 offset:33792
	v_mfma_f32_16x16x32_bf16 v[108:111], v[166:169], v[162:165], v[108:111]
	v_mfma_f32_16x16x32_bf16 v[120:123], v[166:169], v[178:181], v[120:123]
	v_mfma_f32_16x16x32_bf16 v[132:135], v[166:169], v[222:225], v[132:135]
	s_mov_b32 m0, s43
	v_mfma_f32_16x16x32_bf16 v[140:143], v[166:169], v[226:229], v[140:143]
	global_load_lds_dwordx4 v4, s[50:51]
	ds_read_b128 v[166:169], v6 offset:1024
	v_mfma_f32_16x16x32_bf16 v[112:115], v[214:217], v[162:165], v[112:115]
	v_mfma_f32_16x16x32_bf16 v[52:55], v[218:221], v[162:165], v[52:55]
	ds_read_b128 v[162:165], v7 offset:35840
	v_mfma_f32_16x16x32_bf16 v[124:127], v[214:217], v[178:181], v[124:127]
	v_mfma_f32_16x16x32_bf16 v[68:71], v[218:221], v[178:181], v[68:71]
	ds_read_b128 v[178:181], v6 offset:3072
	s_mov_b32 m0, s44
	v_mfma_f32_16x16x32_bf16 v[136:139], v[214:217], v[222:225], v[136:139]
	global_load_lds_dwordx4 v4, s[52:53]
	v_mfma_f32_16x16x32_bf16 v[84:87], v[218:221], v[222:225], v[84:87]
	ds_read_b128 v[222:225], v6 offset:5120
	v_mfma_f32_16x16x32_bf16 v[150:153], v[214:217], v[226:229], v[150:153]
	ds_read_b128 v[214:217], v7 offset:37888
	v_mfma_f32_16x16x32_bf16 v[154:157], v[218:221], v[226:229], v[154:157]
	ds_read_b128 v[218:221], v7 offset:39936
	ds_read_b128 v[226:229], v6 offset:7168
	s_waitcnt lgkmcnt(6)
	v_mfma_f32_16x16x32_bf16 v[40:43], v[158:161], v[166:169], v[40:43]
	s_waitcnt lgkmcnt(5)
	s_mov_b32 m0, s45
	v_mfma_f32_16x16x32_bf16 v[44:47], v[162:165], v[166:169], v[44:47]
	global_load_lds_dwordx4 v146, s[50:51]
	s_waitcnt lgkmcnt(4)
	v_mfma_f32_16x16x32_bf16 v[56:59], v[158:161], v[178:181], v[56:59]
	v_mfma_f32_16x16x32_bf16 v[60:63], v[162:165], v[178:181], v[60:63]
	s_waitcnt lgkmcnt(3)
	v_mfma_f32_16x16x32_bf16 v[72:75], v[158:161], v[222:225], v[72:75]
	v_mfma_f32_16x16x32_bf16 v[76:79], v[162:165], v[222:225], v[76:79]
	s_waitcnt lgkmcnt(2)
	s_mov_b32 m0, s46
	v_mfma_f32_16x16x32_bf16 v[48:51], v[214:217], v[166:169], v[48:51]
	global_load_lds_dwordx4 v146, s[52:53]
	s_waitcnt lgkmcnt(1)
	v_mfma_f32_16x16x32_bf16 v[174:177], v[218:221], v[166:169], v[174:177]
	ds_read_b128 v[166:169], v6 offset:9216
	v_mfma_f32_16x16x32_bf16 v[64:67], v[214:217], v[178:181], v[64:67]
	v_mfma_f32_16x16x32_bf16 v[170:173], v[218:221], v[178:181], v[170:173]
	ds_read_b128 v[178:181], v6 offset:11264
	v_mfma_f32_16x16x32_bf16 v[80:83], v[214:217], v[222:225], v[80:83]
	v_mfma_f32_16x16x32_bf16 v[32:35], v[218:221], v[222:225], v[32:35]
	ds_read_b128 v[222:225], v6 offset:13312
	s_waitcnt lgkmcnt(3)
	v_mfma_f32_16x16x32_bf16 v[88:91], v[158:161], v[226:229], v[88:91]
	v_mfma_f32_16x16x32_bf16 v[92:95], v[162:165], v[226:229], v[92:95]
	v_mfma_f32_16x16x32_bf16 v[96:99], v[214:217], v[226:229], v[96:99]
	v_mfma_f32_16x16x32_bf16 v[36:39], v[218:221], v[226:229], v[36:39]
	ds_read_b128 v[226:229], v6 offset:15360
	s_waitcnt lgkmcnt(3)
	v_mfma_f32_16x16x32_bf16 v[104:107], v[158:161], v[166:169], v[104:107]
	v_mfma_f32_16x16x32_bf16 v[108:111], v[162:165], v[166:169], v[108:111]
	v_mfma_f32_16x16x32_bf16 v[112:115], v[214:217], v[166:169], v[112:115]
	v_mfma_f32_16x16x32_bf16 v[52:55], v[218:221], v[166:169], v[52:55]
	s_waitcnt lgkmcnt(2)
	v_mfma_f32_16x16x32_bf16 v[116:119], v[158:161], v[178:181], v[116:119]
	v_mfma_f32_16x16x32_bf16 v[120:123], v[162:165], v[178:181], v[120:123]
	v_mfma_f32_16x16x32_bf16 v[124:127], v[214:217], v[178:181], v[124:127]
	v_mfma_f32_16x16x32_bf16 v[68:71], v[218:221], v[178:181], v[68:71]
	s_waitcnt lgkmcnt(1)
	v_mfma_f32_16x16x32_bf16 v[128:131], v[158:161], v[222:225], v[128:131]
	v_mfma_f32_16x16x32_bf16 v[132:135], v[162:165], v[222:225], v[132:135]
	v_mfma_f32_16x16x32_bf16 v[136:139], v[214:217], v[222:225], v[136:139]
	v_mfma_f32_16x16x32_bf16 v[84:87], v[218:221], v[222:225], v[84:87]
	s_waitcnt lgkmcnt(0)
	v_mfma_f32_16x16x32_bf16 v[100:103], v[158:161], v[226:229], v[100:103]
	v_mfma_f32_16x16x32_bf16 v[140:143], v[162:165], v[226:229], v[140:143]
	v_mfma_f32_16x16x32_bf16 v[150:153], v[214:217], v[226:229], v[150:153]
	v_mfma_f32_16x16x32_bf16 v[154:157], v[218:221], v[226:229], v[154:157]
	s_add_u32 s50, s14, 0x300
	s_addc_u32 s51, s15, 0
	s_add_u32 s52, s20, 0x300
	s_waitcnt vmcnt(0)
	s_barrier
	s_addc_u32 s53, s21, 0
	ds_read_b128 v[158:161], v8
	ds_read_b128 v[162:165], v12
	ds_read_b128 v[166:169], v9
	ds_read_b128 v[178:181], v13
	ds_read_b128 v[214:217], v11
	ds_read_b128 v[218:221], v10
	ds_read_b128 v[222:225], v14
	ds_read_b128 v[226:229], v15
	s_waitcnt lgkmcnt(6)
	v_mfma_f32_16x16x32_bf16 v[40:43], v[158:161], v[162:165], v[40:43]
	s_waitcnt lgkmcnt(5)
	v_mfma_f32_16x16x32_bf16 v[44:47], v[166:169], v[162:165], v[44:47]
	s_waitcnt lgkmcnt(4)
	v_mfma_f32_16x16x32_bf16 v[56:59], v[158:161], v[178:181], v[56:59]
	s_mov_b32 m0, s1
	v_mfma_f32_16x16x32_bf16 v[60:63], v[166:169], v[178:181], v[60:63]
	global_load_lds_dwordx4 v0, s[50:51]
	s_waitcnt lgkmcnt(3)
	v_mfma_f32_16x16x32_bf16 v[48:51], v[214:217], v[162:165], v[48:51]
	v_mfma_f32_16x16x32_bf16 v[64:67], v[214:217], v[178:181], v[64:67]
	s_waitcnt lgkmcnt(2)
	v_mfma_f32_16x16x32_bf16 v[174:177], v[218:221], v[162:165], v[174:177]
	ds_read_b128 v[162:165], v16
	v_mfma_f32_16x16x32_bf16 v[170:173], v[218:221], v[178:181], v[170:173]
	ds_read_b128 v[178:181], v17
	s_waitcnt lgkmcnt(3)
	s_mov_b32 m0, s34
	v_mfma_f32_16x16x32_bf16 v[72:75], v[158:161], v[222:225], v[72:75]
	global_load_lds_dwordx4 v0, s[52:53]
	v_mfma_f32_16x16x32_bf16 v[76:79], v[166:169], v[222:225], v[76:79]
	v_mfma_f32_16x16x32_bf16 v[80:83], v[214:217], v[222:225], v[80:83]
	v_mfma_f32_16x16x32_bf16 v[32:35], v[218:221], v[222:225], v[32:35]
	ds_read_b128 v[222:225], v18
	s_waitcnt lgkmcnt(3)
	v_mfma_f32_16x16x32_bf16 v[88:91], v[158:161], v[226:229], v[88:91]
	s_mov_b32 m0, s35
	v_mfma_f32_16x16x32_bf16 v[92:95], v[166:169], v[226:229], v[92:95]
	global_load_lds_dwordx4 v2, s[50:51]
	v_mfma_f32_16x16x32_bf16 v[96:99], v[214:217], v[226:229], v[96:99]
	v_mfma_f32_16x16x32_bf16 v[36:39], v[218:221], v[226:229], v[36:39]
	ds_read_b128 v[226:229], v19
	s_waitcnt lgkmcnt(3)
	v_mfma_f32_16x16x32_bf16 v[104:107], v[158:161], v[162:165], v[104:107]
	s_waitcnt lgkmcnt(2)
	v_mfma_f32_16x16x32_bf16 v[116:119], v[158:161], v[178:181], v[116:119]
	s_waitcnt lgkmcnt(1)
	s_mov_b32 m0, s36
	v_mfma_f32_16x16x32_bf16 v[128:131], v[158:161], v[222:225], v[128:131]
	global_load_lds_dwordx4 v2, s[52:53]
	s_waitcnt lgkmcnt(0)
	v_mfma_f32_16x16x32_bf16 v[100:103], v[158:161], v[226:229], v[100:103]
	ds_read_b128 v[158:161], v20
	v_mfma_f32_16x16x32_bf16 v[108:111], v[166:169], v[162:165], v[108:111]
	v_mfma_f32_16x16x32_bf16 v[120:123], v[166:169], v[178:181], v[120:123]
	v_mfma_f32_16x16x32_bf16 v[132:135], v[166:169], v[222:225], v[132:135]
	s_mov_b32 m0, s37
	v_mfma_f32_16x16x32_bf16 v[140:143], v[166:169], v[226:229], v[140:143]
	global_load_lds_dwordx4 v4, s[50:51]
	ds_read_b128 v[166:169], v24
	v_mfma_f32_16x16x32_bf16 v[112:115], v[214:217], v[162:165], v[112:115]
	v_mfma_f32_16x16x32_bf16 v[52:55], v[218:221], v[162:165], v[52:55]
	ds_read_b128 v[162:165], v21
	v_mfma_f32_16x16x32_bf16 v[124:127], v[214:217], v[178:181], v[124:127]
	v_mfma_f32_16x16x32_bf16 v[68:71], v[218:221], v[178:181], v[68:71]
	ds_read_b128 v[178:181], v25
	s_mov_b32 m0, s38
	v_mfma_f32_16x16x32_bf16 v[136:139], v[214:217], v[222:225], v[136:139]
	global_load_lds_dwordx4 v4, s[52:53]
	v_mfma_f32_16x16x32_bf16 v[84:87], v[218:221], v[222:225], v[84:87]
	ds_read_b128 v[222:225], v26
	v_mfma_f32_16x16x32_bf16 v[150:153], v[214:217], v[226:229], v[150:153]
	ds_read_b128 v[214:217], v23
	v_mfma_f32_16x16x32_bf16 v[154:157], v[218:221], v[226:229], v[154:157]
	ds_read_b128 v[218:221], v22
	ds_read_b128 v[226:229], v27
	s_waitcnt lgkmcnt(6)
	v_mfma_f32_16x16x32_bf16 v[40:43], v[158:161], v[166:169], v[40:43]
	s_waitcnt lgkmcnt(5)
	s_mov_b32 m0, s39
	v_mfma_f32_16x16x32_bf16 v[44:47], v[162:165], v[166:169], v[44:47]
	global_load_lds_dwordx4 v146, s[50:51]
	s_waitcnt lgkmcnt(4)
	v_mfma_f32_16x16x32_bf16 v[56:59], v[158:161], v[178:181], v[56:59]
	v_mfma_f32_16x16x32_bf16 v[60:63], v[162:165], v[178:181], v[60:63]
	s_waitcnt lgkmcnt(3)
	v_mfma_f32_16x16x32_bf16 v[72:75], v[158:161], v[222:225], v[72:75]
	v_mfma_f32_16x16x32_bf16 v[76:79], v[162:165], v[222:225], v[76:79]
	s_waitcnt lgkmcnt(2)
	s_mov_b32 m0, s40
	v_mfma_f32_16x16x32_bf16 v[48:51], v[214:217], v[166:169], v[48:51]
	global_load_lds_dwordx4 v146, s[52:53]
	s_waitcnt lgkmcnt(1)
	v_mfma_f32_16x16x32_bf16 v[174:177], v[218:221], v[166:169], v[174:177]
	ds_read_b128 v[166:169], v28
	v_mfma_f32_16x16x32_bf16 v[64:67], v[214:217], v[178:181], v[64:67]
	v_mfma_f32_16x16x32_bf16 v[170:173], v[218:221], v[178:181], v[170:173]
	ds_read_b128 v[178:181], v29
	v_mfma_f32_16x16x32_bf16 v[80:83], v[214:217], v[222:225], v[80:83]
	v_mfma_f32_16x16x32_bf16 v[32:35], v[218:221], v[222:225], v[32:35]
	ds_read_b128 v[222:225], v30
	s_waitcnt lgkmcnt(3)
	v_mfma_f32_16x16x32_bf16 v[88:91], v[158:161], v[226:229], v[88:91]
	v_mfma_f32_16x16x32_bf16 v[92:95], v[162:165], v[226:229], v[92:95]
	v_mfma_f32_16x16x32_bf16 v[96:99], v[214:217], v[226:229], v[96:99]
	v_mfma_f32_16x16x32_bf16 v[36:39], v[218:221], v[226:229], v[36:39]
	ds_read_b128 v[226:229], v31
	s_waitcnt lgkmcnt(3)
	v_mfma_f32_16x16x32_bf16 v[104:107], v[158:161], v[166:169], v[104:107]
	v_mfma_f32_16x16x32_bf16 v[108:111], v[162:165], v[166:169], v[108:111]
	v_mfma_f32_16x16x32_bf16 v[112:115], v[214:217], v[166:169], v[112:115]
	v_mfma_f32_16x16x32_bf16 v[52:55], v[218:221], v[166:169], v[52:55]
	s_waitcnt lgkmcnt(2)
	v_mfma_f32_16x16x32_bf16 v[116:119], v[158:161], v[178:181], v[116:119]
	v_mfma_f32_16x16x32_bf16 v[120:123], v[162:165], v[178:181], v[120:123]
	v_mfma_f32_16x16x32_bf16 v[124:127], v[214:217], v[178:181], v[124:127]
	v_mfma_f32_16x16x32_bf16 v[68:71], v[218:221], v[178:181], v[68:71]
	s_waitcnt lgkmcnt(1)
	v_mfma_f32_16x16x32_bf16 v[128:131], v[158:161], v[222:225], v[128:131]
	v_mfma_f32_16x16x32_bf16 v[132:135], v[162:165], v[222:225], v[132:135]
	v_mfma_f32_16x16x32_bf16 v[136:139], v[214:217], v[222:225], v[136:139]
	v_mfma_f32_16x16x32_bf16 v[84:87], v[218:221], v[222:225], v[84:87]
	s_waitcnt lgkmcnt(0)
	v_mfma_f32_16x16x32_bf16 v[100:103], v[158:161], v[226:229], v[100:103]
	v_mfma_f32_16x16x32_bf16 v[140:143], v[162:165], v[226:229], v[140:143]
	v_mfma_f32_16x16x32_bf16 v[150:153], v[214:217], v[226:229], v[150:153]
	v_mfma_f32_16x16x32_bf16 v[154:157], v[218:221], v[226:229], v[154:157]
	s_add_u32 s50, s14, 0x380
	s_addc_u32 s51, s15, 0
	s_add_u32 s52, s20, 0x380
	s_waitcnt vmcnt(0)
	s_barrier
	s_addc_u32 s53, s21, 0
	ds_read_b128 v[158:161], v7 offset:32768
	ds_read_b128 v[162:165], v6
	ds_read_b128 v[166:169], v7 offset:34816
	ds_read_b128 v[178:181], v6 offset:2048
	ds_read_b128 v[214:217], v7 offset:36864
	ds_read_b128 v[218:221], v7 offset:38912
	ds_read_b128 v[222:225], v6 offset:4096
	ds_read_b128 v[226:229], v6 offset:6144
	s_waitcnt lgkmcnt(6)
	v_mfma_f32_16x16x32_bf16 v[40:43], v[158:161], v[162:165], v[40:43]
	s_waitcnt lgkmcnt(5)
	v_mfma_f32_16x16x32_bf16 v[44:47], v[166:169], v[162:165], v[44:47]
	s_waitcnt lgkmcnt(4)
	v_mfma_f32_16x16x32_bf16 v[56:59], v[158:161], v[178:181], v[56:59]
	s_mov_b32 m0, s27
	v_mfma_f32_16x16x32_bf16 v[60:63], v[166:169], v[178:181], v[60:63]
	global_load_lds_dwordx4 v0, s[50:51]
	s_waitcnt lgkmcnt(3)
	v_mfma_f32_16x16x32_bf16 v[48:51], v[214:217], v[162:165], v[48:51]
	v_mfma_f32_16x16x32_bf16 v[64:67], v[214:217], v[178:181], v[64:67]
	s_waitcnt lgkmcnt(2)
	v_mfma_f32_16x16x32_bf16 v[174:177], v[218:221], v[162:165], v[174:177]
	ds_read_b128 v[162:165], v6 offset:8192
	v_mfma_f32_16x16x32_bf16 v[170:173], v[218:221], v[178:181], v[170:173]
	ds_read_b128 v[178:181], v6 offset:10240
	s_waitcnt lgkmcnt(3)
	s_mov_b32 m0, s26
	v_mfma_f32_16x16x32_bf16 v[72:75], v[158:161], v[222:225], v[72:75]
	global_load_lds_dwordx4 v0, s[52:53]
	v_mfma_f32_16x16x32_bf16 v[76:79], v[166:169], v[222:225], v[76:79]
	v_mfma_f32_16x16x32_bf16 v[80:83], v[214:217], v[222:225], v[80:83]
	v_mfma_f32_16x16x32_bf16 v[32:35], v[218:221], v[222:225], v[32:35]
	ds_read_b128 v[222:225], v6 offset:12288
	s_waitcnt lgkmcnt(3)
	v_mfma_f32_16x16x32_bf16 v[88:91], v[158:161], v[226:229], v[88:91]
	s_mov_b32 m0, s41
	v_mfma_f32_16x16x32_bf16 v[92:95], v[166:169], v[226:229], v[92:95]
	global_load_lds_dwordx4 v2, s[50:51]
	v_mfma_f32_16x16x32_bf16 v[96:99], v[214:217], v[226:229], v[96:99]
	v_mfma_f32_16x16x32_bf16 v[36:39], v[218:221], v[226:229], v[36:39]
	ds_read_b128 v[226:229], v6 offset:14336
	s_waitcnt lgkmcnt(3)
	v_mfma_f32_16x16x32_bf16 v[104:107], v[158:161], v[162:165], v[104:107]
	s_waitcnt lgkmcnt(2)
	v_mfma_f32_16x16x32_bf16 v[116:119], v[158:161], v[178:181], v[116:119]
	s_waitcnt lgkmcnt(1)
	s_mov_b32 m0, s42
	v_mfma_f32_16x16x32_bf16 v[128:131], v[158:161], v[222:225], v[128:131]
	global_load_lds_dwordx4 v2, s[52:53]
	s_waitcnt lgkmcnt(0)
	v_mfma_f32_16x16x32_bf16 v[100:103], v[158:161], v[226:229], v[100:103]
	ds_read_b128 v[158:161], v7 offset:33792
	v_mfma_f32_16x16x32_bf16 v[108:111], v[166:169], v[162:165], v[108:111]
	v_mfma_f32_16x16x32_bf16 v[120:123], v[166:169], v[178:181], v[120:123]
	v_mfma_f32_16x16x32_bf16 v[132:135], v[166:169], v[222:225], v[132:135]
	s_mov_b32 m0, s43
	v_mfma_f32_16x16x32_bf16 v[140:143], v[166:169], v[226:229], v[140:143]
	global_load_lds_dwordx4 v4, s[50:51]
	ds_read_b128 v[166:169], v6 offset:1024
	v_mfma_f32_16x16x32_bf16 v[112:115], v[214:217], v[162:165], v[112:115]
	v_mfma_f32_16x16x32_bf16 v[52:55], v[218:221], v[162:165], v[52:55]
	ds_read_b128 v[162:165], v7 offset:35840
	v_mfma_f32_16x16x32_bf16 v[124:127], v[214:217], v[178:181], v[124:127]
	v_mfma_f32_16x16x32_bf16 v[68:71], v[218:221], v[178:181], v[68:71]
	ds_read_b128 v[178:181], v6 offset:3072
	s_mov_b32 m0, s44
	v_mfma_f32_16x16x32_bf16 v[136:139], v[214:217], v[222:225], v[136:139]
	global_load_lds_dwordx4 v4, s[52:53]
	v_mfma_f32_16x16x32_bf16 v[84:87], v[218:221], v[222:225], v[84:87]
	ds_read_b128 v[222:225], v6 offset:5120
	v_mfma_f32_16x16x32_bf16 v[150:153], v[214:217], v[226:229], v[150:153]
	ds_read_b128 v[214:217], v7 offset:37888
	v_mfma_f32_16x16x32_bf16 v[154:157], v[218:221], v[226:229], v[154:157]
	ds_read_b128 v[218:221], v7 offset:39936
	ds_read_b128 v[226:229], v6 offset:7168
	s_waitcnt lgkmcnt(6)
	v_mfma_f32_16x16x32_bf16 v[40:43], v[158:161], v[166:169], v[40:43]
	s_waitcnt lgkmcnt(5)
	s_mov_b32 m0, s45
	v_mfma_f32_16x16x32_bf16 v[44:47], v[162:165], v[166:169], v[44:47]
	global_load_lds_dwordx4 v146, s[50:51]
	s_waitcnt lgkmcnt(4)
	v_mfma_f32_16x16x32_bf16 v[56:59], v[158:161], v[178:181], v[56:59]
	v_mfma_f32_16x16x32_bf16 v[60:63], v[162:165], v[178:181], v[60:63]
	s_waitcnt lgkmcnt(3)
	v_mfma_f32_16x16x32_bf16 v[72:75], v[158:161], v[222:225], v[72:75]
	v_mfma_f32_16x16x32_bf16 v[76:79], v[162:165], v[222:225], v[76:79]
	s_waitcnt lgkmcnt(2)
	s_mov_b32 m0, s46
	v_mfma_f32_16x16x32_bf16 v[48:51], v[214:217], v[166:169], v[48:51]
	global_load_lds_dwordx4 v146, s[52:53]
	s_waitcnt lgkmcnt(1)
	v_mfma_f32_16x16x32_bf16 v[174:177], v[218:221], v[166:169], v[174:177]
	ds_read_b128 v[166:169], v6 offset:9216
	v_mfma_f32_16x16x32_bf16 v[64:67], v[214:217], v[178:181], v[64:67]
	v_mfma_f32_16x16x32_bf16 v[170:173], v[218:221], v[178:181], v[170:173]
	ds_read_b128 v[178:181], v6 offset:11264
	v_mfma_f32_16x16x32_bf16 v[80:83], v[214:217], v[222:225], v[80:83]
	v_mfma_f32_16x16x32_bf16 v[32:35], v[218:221], v[222:225], v[32:35]
	ds_read_b128 v[222:225], v6 offset:13312
	s_waitcnt lgkmcnt(3)
	v_mfma_f32_16x16x32_bf16 v[88:91], v[158:161], v[226:229], v[88:91]
	v_mfma_f32_16x16x32_bf16 v[92:95], v[162:165], v[226:229], v[92:95]
	v_mfma_f32_16x16x32_bf16 v[96:99], v[214:217], v[226:229], v[96:99]
	v_mfma_f32_16x16x32_bf16 v[36:39], v[218:221], v[226:229], v[36:39]
	ds_read_b128 v[226:229], v6 offset:15360
	s_waitcnt lgkmcnt(3)
	v_mfma_f32_16x16x32_bf16 v[104:107], v[158:161], v[166:169], v[104:107]
	v_mfma_f32_16x16x32_bf16 v[108:111], v[162:165], v[166:169], v[108:111]
	v_mfma_f32_16x16x32_bf16 v[112:115], v[214:217], v[166:169], v[112:115]
	v_mfma_f32_16x16x32_bf16 v[52:55], v[218:221], v[166:169], v[52:55]
	s_waitcnt lgkmcnt(2)
	v_mfma_f32_16x16x32_bf16 v[116:119], v[158:161], v[178:181], v[116:119]
	v_mfma_f32_16x16x32_bf16 v[120:123], v[162:165], v[178:181], v[120:123]
	v_mfma_f32_16x16x32_bf16 v[124:127], v[214:217], v[178:181], v[124:127]
	v_mfma_f32_16x16x32_bf16 v[68:71], v[218:221], v[178:181], v[68:71]
	s_waitcnt lgkmcnt(1)
	v_mfma_f32_16x16x32_bf16 v[128:131], v[158:161], v[222:225], v[128:131]
	v_mfma_f32_16x16x32_bf16 v[132:135], v[162:165], v[222:225], v[132:135]
	v_mfma_f32_16x16x32_bf16 v[136:139], v[214:217], v[222:225], v[136:139]
	v_mfma_f32_16x16x32_bf16 v[84:87], v[218:221], v[222:225], v[84:87]
	s_waitcnt lgkmcnt(0)
	v_mfma_f32_16x16x32_bf16 v[100:103], v[158:161], v[226:229], v[100:103]
	v_mfma_f32_16x16x32_bf16 v[140:143], v[162:165], v[226:229], v[140:143]
	v_mfma_f32_16x16x32_bf16 v[150:153], v[214:217], v[226:229], v[150:153]
	v_mfma_f32_16x16x32_bf16 v[154:157], v[218:221], v[226:229], v[154:157]
	s_add_u32 s50, s14, 0x400
	s_addc_u32 s51, s15, 0
	s_add_u32 s52, s20, 0x400
	s_waitcnt vmcnt(0)
	s_barrier
	s_addc_u32 s53, s21, 0
	ds_read_b128 v[158:161], v8
	ds_read_b128 v[162:165], v12
	ds_read_b128 v[166:169], v9
	ds_read_b128 v[178:181], v13
	ds_read_b128 v[214:217], v11
	ds_read_b128 v[218:221], v10
	ds_read_b128 v[222:225], v14
	ds_read_b128 v[226:229], v15
	s_waitcnt lgkmcnt(6)
	v_mfma_f32_16x16x32_bf16 v[40:43], v[158:161], v[162:165], v[40:43]
	s_waitcnt lgkmcnt(5)
	v_mfma_f32_16x16x32_bf16 v[44:47], v[166:169], v[162:165], v[44:47]
	s_waitcnt lgkmcnt(4)
	v_mfma_f32_16x16x32_bf16 v[56:59], v[158:161], v[178:181], v[56:59]
	s_mov_b32 m0, s1
	v_mfma_f32_16x16x32_bf16 v[60:63], v[166:169], v[178:181], v[60:63]
	global_load_lds_dwordx4 v0, s[50:51]
	s_waitcnt lgkmcnt(3)
	v_mfma_f32_16x16x32_bf16 v[48:51], v[214:217], v[162:165], v[48:51]
	v_mfma_f32_16x16x32_bf16 v[64:67], v[214:217], v[178:181], v[64:67]
	s_waitcnt lgkmcnt(2)
	v_mfma_f32_16x16x32_bf16 v[174:177], v[218:221], v[162:165], v[174:177]
	ds_read_b128 v[162:165], v16
	v_mfma_f32_16x16x32_bf16 v[170:173], v[218:221], v[178:181], v[170:173]
	ds_read_b128 v[178:181], v17
	s_waitcnt lgkmcnt(3)
	s_mov_b32 m0, s34
	v_mfma_f32_16x16x32_bf16 v[72:75], v[158:161], v[222:225], v[72:75]
	global_load_lds_dwordx4 v0, s[52:53]
	v_mfma_f32_16x16x32_bf16 v[76:79], v[166:169], v[222:225], v[76:79]
	v_mfma_f32_16x16x32_bf16 v[80:83], v[214:217], v[222:225], v[80:83]
	v_mfma_f32_16x16x32_bf16 v[32:35], v[218:221], v[222:225], v[32:35]
	ds_read_b128 v[222:225], v18
	s_waitcnt lgkmcnt(3)
	v_mfma_f32_16x16x32_bf16 v[88:91], v[158:161], v[226:229], v[88:91]
	s_mov_b32 m0, s35
	v_mfma_f32_16x16x32_bf16 v[92:95], v[166:169], v[226:229], v[92:95]
	global_load_lds_dwordx4 v2, s[50:51]
	v_mfma_f32_16x16x32_bf16 v[96:99], v[214:217], v[226:229], v[96:99]
	v_mfma_f32_16x16x32_bf16 v[36:39], v[218:221], v[226:229], v[36:39]
	ds_read_b128 v[226:229], v19
	s_waitcnt lgkmcnt(3)
	v_mfma_f32_16x16x32_bf16 v[104:107], v[158:161], v[162:165], v[104:107]
	s_waitcnt lgkmcnt(2)
	v_mfma_f32_16x16x32_bf16 v[116:119], v[158:161], v[178:181], v[116:119]
	s_waitcnt lgkmcnt(1)
	s_mov_b32 m0, s36
	v_mfma_f32_16x16x32_bf16 v[128:131], v[158:161], v[222:225], v[128:131]
	global_load_lds_dwordx4 v2, s[52:53]
	s_waitcnt lgkmcnt(0)
	v_mfma_f32_16x16x32_bf16 v[100:103], v[158:161], v[226:229], v[100:103]
	ds_read_b128 v[158:161], v20
	v_mfma_f32_16x16x32_bf16 v[108:111], v[166:169], v[162:165], v[108:111]
	v_mfma_f32_16x16x32_bf16 v[120:123], v[166:169], v[178:181], v[120:123]
	v_mfma_f32_16x16x32_bf16 v[132:135], v[166:169], v[222:225], v[132:135]
	s_mov_b32 m0, s37
	v_mfma_f32_16x16x32_bf16 v[140:143], v[166:169], v[226:229], v[140:143]
	global_load_lds_dwordx4 v4, s[50:51]
	ds_read_b128 v[166:169], v24
	v_mfma_f32_16x16x32_bf16 v[112:115], v[214:217], v[162:165], v[112:115]
	v_mfma_f32_16x16x32_bf16 v[52:55], v[218:221], v[162:165], v[52:55]
	ds_read_b128 v[162:165], v21
	v_mfma_f32_16x16x32_bf16 v[124:127], v[214:217], v[178:181], v[124:127]
	v_mfma_f32_16x16x32_bf16 v[68:71], v[218:221], v[178:181], v[68:71]
	ds_read_b128 v[178:181], v25
	s_mov_b32 m0, s38
	v_mfma_f32_16x16x32_bf16 v[136:139], v[214:217], v[222:225], v[136:139]
	global_load_lds_dwordx4 v4, s[52:53]
	v_mfma_f32_16x16x32_bf16 v[84:87], v[218:221], v[222:225], v[84:87]
	ds_read_b128 v[222:225], v26
	v_mfma_f32_16x16x32_bf16 v[150:153], v[214:217], v[226:229], v[150:153]
	ds_read_b128 v[214:217], v23
	v_mfma_f32_16x16x32_bf16 v[154:157], v[218:221], v[226:229], v[154:157]
	ds_read_b128 v[218:221], v22
	ds_read_b128 v[226:229], v27
	s_waitcnt lgkmcnt(6)
	v_mfma_f32_16x16x32_bf16 v[40:43], v[158:161], v[166:169], v[40:43]
	s_waitcnt lgkmcnt(5)
	s_mov_b32 m0, s39
	v_mfma_f32_16x16x32_bf16 v[44:47], v[162:165], v[166:169], v[44:47]
	global_load_lds_dwordx4 v146, s[50:51]
	s_waitcnt lgkmcnt(4)
	v_mfma_f32_16x16x32_bf16 v[56:59], v[158:161], v[178:181], v[56:59]
	v_mfma_f32_16x16x32_bf16 v[60:63], v[162:165], v[178:181], v[60:63]
	s_waitcnt lgkmcnt(3)
	v_mfma_f32_16x16x32_bf16 v[72:75], v[158:161], v[222:225], v[72:75]
	v_mfma_f32_16x16x32_bf16 v[76:79], v[162:165], v[222:225], v[76:79]
	s_waitcnt lgkmcnt(2)
	s_mov_b32 m0, s40
	v_mfma_f32_16x16x32_bf16 v[48:51], v[214:217], v[166:169], v[48:51]
	global_load_lds_dwordx4 v146, s[52:53]
	s_waitcnt lgkmcnt(1)
	v_mfma_f32_16x16x32_bf16 v[174:177], v[218:221], v[166:169], v[174:177]
	ds_read_b128 v[166:169], v28
	v_mfma_f32_16x16x32_bf16 v[64:67], v[214:217], v[178:181], v[64:67]
	v_mfma_f32_16x16x32_bf16 v[170:173], v[218:221], v[178:181], v[170:173]
	ds_read_b128 v[178:181], v29
	v_mfma_f32_16x16x32_bf16 v[80:83], v[214:217], v[222:225], v[80:83]
	v_mfma_f32_16x16x32_bf16 v[32:35], v[218:221], v[222:225], v[32:35]
	ds_read_b128 v[222:225], v30
	s_waitcnt lgkmcnt(3)
	v_mfma_f32_16x16x32_bf16 v[88:91], v[158:161], v[226:229], v[88:91]
	v_mfma_f32_16x16x32_bf16 v[92:95], v[162:165], v[226:229], v[92:95]
	v_mfma_f32_16x16x32_bf16 v[96:99], v[214:217], v[226:229], v[96:99]
	v_mfma_f32_16x16x32_bf16 v[36:39], v[218:221], v[226:229], v[36:39]
	ds_read_b128 v[226:229], v31
	s_waitcnt lgkmcnt(3)
	v_mfma_f32_16x16x32_bf16 v[104:107], v[158:161], v[166:169], v[104:107]
	v_mfma_f32_16x16x32_bf16 v[108:111], v[162:165], v[166:169], v[108:111]
	v_mfma_f32_16x16x32_bf16 v[112:115], v[214:217], v[166:169], v[112:115]
	v_mfma_f32_16x16x32_bf16 v[52:55], v[218:221], v[166:169], v[52:55]
	s_waitcnt lgkmcnt(2)
	v_mfma_f32_16x16x32_bf16 v[116:119], v[158:161], v[178:181], v[116:119]
	v_mfma_f32_16x16x32_bf16 v[120:123], v[162:165], v[178:181], v[120:123]
	v_mfma_f32_16x16x32_bf16 v[124:127], v[214:217], v[178:181], v[124:127]
	v_mfma_f32_16x16x32_bf16 v[68:71], v[218:221], v[178:181], v[68:71]
	s_waitcnt lgkmcnt(1)
	v_mfma_f32_16x16x32_bf16 v[128:131], v[158:161], v[222:225], v[128:131]
	v_mfma_f32_16x16x32_bf16 v[132:135], v[162:165], v[222:225], v[132:135]
	v_mfma_f32_16x16x32_bf16 v[136:139], v[214:217], v[222:225], v[136:139]
	v_mfma_f32_16x16x32_bf16 v[84:87], v[218:221], v[222:225], v[84:87]
	s_waitcnt lgkmcnt(0)
	v_mfma_f32_16x16x32_bf16 v[100:103], v[158:161], v[226:229], v[100:103]
	v_mfma_f32_16x16x32_bf16 v[140:143], v[162:165], v[226:229], v[140:143]
	v_mfma_f32_16x16x32_bf16 v[150:153], v[214:217], v[226:229], v[150:153]
	v_mfma_f32_16x16x32_bf16 v[154:157], v[218:221], v[226:229], v[154:157]
	s_add_u32 s50, s14, 0x480
	s_addc_u32 s51, s15, 0
	s_add_u32 s52, s20, 0x480
	s_waitcnt vmcnt(0)
	s_barrier
	s_addc_u32 s53, s21, 0
	ds_read_b128 v[158:161], v7 offset:32768
	ds_read_b128 v[162:165], v6
	ds_read_b128 v[166:169], v7 offset:34816
	ds_read_b128 v[178:181], v6 offset:2048
	ds_read_b128 v[214:217], v7 offset:36864
	ds_read_b128 v[218:221], v7 offset:38912
	ds_read_b128 v[222:225], v6 offset:4096
	ds_read_b128 v[226:229], v6 offset:6144
	s_waitcnt lgkmcnt(6)
	v_mfma_f32_16x16x32_bf16 v[40:43], v[158:161], v[162:165], v[40:43]
	s_waitcnt lgkmcnt(5)
	v_mfma_f32_16x16x32_bf16 v[44:47], v[166:169], v[162:165], v[44:47]
	s_waitcnt lgkmcnt(4)
	v_mfma_f32_16x16x32_bf16 v[56:59], v[158:161], v[178:181], v[56:59]
	s_mov_b32 m0, s27
	v_mfma_f32_16x16x32_bf16 v[60:63], v[166:169], v[178:181], v[60:63]
	global_load_lds_dwordx4 v0, s[50:51]
	s_waitcnt lgkmcnt(3)
	v_mfma_f32_16x16x32_bf16 v[48:51], v[214:217], v[162:165], v[48:51]
	v_mfma_f32_16x16x32_bf16 v[64:67], v[214:217], v[178:181], v[64:67]
	s_waitcnt lgkmcnt(2)
	v_mfma_f32_16x16x32_bf16 v[174:177], v[218:221], v[162:165], v[174:177]
	ds_read_b128 v[162:165], v6 offset:8192
	v_mfma_f32_16x16x32_bf16 v[170:173], v[218:221], v[178:181], v[170:173]
	ds_read_b128 v[178:181], v6 offset:10240
	s_waitcnt lgkmcnt(3)
	s_mov_b32 m0, s26
	v_mfma_f32_16x16x32_bf16 v[72:75], v[158:161], v[222:225], v[72:75]
	global_load_lds_dwordx4 v0, s[52:53]
	v_mfma_f32_16x16x32_bf16 v[76:79], v[166:169], v[222:225], v[76:79]
	v_mfma_f32_16x16x32_bf16 v[80:83], v[214:217], v[222:225], v[80:83]
	v_mfma_f32_16x16x32_bf16 v[32:35], v[218:221], v[222:225], v[32:35]
	ds_read_b128 v[222:225], v6 offset:12288
	s_waitcnt lgkmcnt(3)
	v_mfma_f32_16x16x32_bf16 v[88:91], v[158:161], v[226:229], v[88:91]
	s_mov_b32 m0, s41
	v_mfma_f32_16x16x32_bf16 v[92:95], v[166:169], v[226:229], v[92:95]
	global_load_lds_dwordx4 v2, s[50:51]
	v_mfma_f32_16x16x32_bf16 v[96:99], v[214:217], v[226:229], v[96:99]
	v_mfma_f32_16x16x32_bf16 v[36:39], v[218:221], v[226:229], v[36:39]
	ds_read_b128 v[226:229], v6 offset:14336
	s_waitcnt lgkmcnt(3)
	v_mfma_f32_16x16x32_bf16 v[104:107], v[158:161], v[162:165], v[104:107]
	s_waitcnt lgkmcnt(2)
	v_mfma_f32_16x16x32_bf16 v[116:119], v[158:161], v[178:181], v[116:119]
	s_waitcnt lgkmcnt(1)
	s_mov_b32 m0, s42
	v_mfma_f32_16x16x32_bf16 v[128:131], v[158:161], v[222:225], v[128:131]
	global_load_lds_dwordx4 v2, s[52:53]
	s_waitcnt lgkmcnt(0)
	v_mfma_f32_16x16x32_bf16 v[100:103], v[158:161], v[226:229], v[100:103]
	ds_read_b128 v[158:161], v7 offset:33792
	v_mfma_f32_16x16x32_bf16 v[108:111], v[166:169], v[162:165], v[108:111]
	v_mfma_f32_16x16x32_bf16 v[120:123], v[166:169], v[178:181], v[120:123]
	v_mfma_f32_16x16x32_bf16 v[132:135], v[166:169], v[222:225], v[132:135]
	s_mov_b32 m0, s43
	v_mfma_f32_16x16x32_bf16 v[140:143], v[166:169], v[226:229], v[140:143]
	global_load_lds_dwordx4 v4, s[50:51]
	ds_read_b128 v[166:169], v6 offset:1024
	v_mfma_f32_16x16x32_bf16 v[112:115], v[214:217], v[162:165], v[112:115]
	v_mfma_f32_16x16x32_bf16 v[52:55], v[218:221], v[162:165], v[52:55]
	ds_read_b128 v[162:165], v7 offset:35840
	v_mfma_f32_16x16x32_bf16 v[124:127], v[214:217], v[178:181], v[124:127]
	v_mfma_f32_16x16x32_bf16 v[68:71], v[218:221], v[178:181], v[68:71]
	ds_read_b128 v[178:181], v6 offset:3072
	s_mov_b32 m0, s44
	v_mfma_f32_16x16x32_bf16 v[136:139], v[214:217], v[222:225], v[136:139]
	global_load_lds_dwordx4 v4, s[52:53]
	v_mfma_f32_16x16x32_bf16 v[84:87], v[218:221], v[222:225], v[84:87]
	ds_read_b128 v[222:225], v6 offset:5120
	v_mfma_f32_16x16x32_bf16 v[150:153], v[214:217], v[226:229], v[150:153]
	ds_read_b128 v[214:217], v7 offset:37888
	v_mfma_f32_16x16x32_bf16 v[154:157], v[218:221], v[226:229], v[154:157]
	ds_read_b128 v[218:221], v7 offset:39936
	ds_read_b128 v[226:229], v6 offset:7168
	s_waitcnt lgkmcnt(6)
	v_mfma_f32_16x16x32_bf16 v[40:43], v[158:161], v[166:169], v[40:43]
	s_waitcnt lgkmcnt(5)
	s_mov_b32 m0, s45
	v_mfma_f32_16x16x32_bf16 v[44:47], v[162:165], v[166:169], v[44:47]
	global_load_lds_dwordx4 v146, s[50:51]
	s_waitcnt lgkmcnt(4)
	v_mfma_f32_16x16x32_bf16 v[56:59], v[158:161], v[178:181], v[56:59]
	v_mfma_f32_16x16x32_bf16 v[60:63], v[162:165], v[178:181], v[60:63]
	s_waitcnt lgkmcnt(3)
	v_mfma_f32_16x16x32_bf16 v[72:75], v[158:161], v[222:225], v[72:75]
	v_mfma_f32_16x16x32_bf16 v[76:79], v[162:165], v[222:225], v[76:79]
	s_waitcnt lgkmcnt(2)
	s_mov_b32 m0, s46
	v_mfma_f32_16x16x32_bf16 v[48:51], v[214:217], v[166:169], v[48:51]
	global_load_lds_dwordx4 v146, s[52:53]
	s_waitcnt lgkmcnt(1)
	v_mfma_f32_16x16x32_bf16 v[174:177], v[218:221], v[166:169], v[174:177]
	ds_read_b128 v[166:169], v6 offset:9216
	v_mfma_f32_16x16x32_bf16 v[64:67], v[214:217], v[178:181], v[64:67]
	v_mfma_f32_16x16x32_bf16 v[170:173], v[218:221], v[178:181], v[170:173]
	ds_read_b128 v[178:181], v6 offset:11264
	v_mfma_f32_16x16x32_bf16 v[80:83], v[214:217], v[222:225], v[80:83]
	v_mfma_f32_16x16x32_bf16 v[32:35], v[218:221], v[222:225], v[32:35]
	ds_read_b128 v[222:225], v6 offset:13312
	s_waitcnt lgkmcnt(3)
	v_mfma_f32_16x16x32_bf16 v[88:91], v[158:161], v[226:229], v[88:91]
	v_mfma_f32_16x16x32_bf16 v[92:95], v[162:165], v[226:229], v[92:95]
	v_mfma_f32_16x16x32_bf16 v[96:99], v[214:217], v[226:229], v[96:99]
	v_mfma_f32_16x16x32_bf16 v[36:39], v[218:221], v[226:229], v[36:39]
	ds_read_b128 v[226:229], v6 offset:15360
	s_waitcnt lgkmcnt(3)
	v_mfma_f32_16x16x32_bf16 v[104:107], v[158:161], v[166:169], v[104:107]
	v_mfma_f32_16x16x32_bf16 v[108:111], v[162:165], v[166:169], v[108:111]
	v_mfma_f32_16x16x32_bf16 v[112:115], v[214:217], v[166:169], v[112:115]
	v_mfma_f32_16x16x32_bf16 v[52:55], v[218:221], v[166:169], v[52:55]
	s_waitcnt lgkmcnt(2)
	v_mfma_f32_16x16x32_bf16 v[116:119], v[158:161], v[178:181], v[116:119]
	v_mfma_f32_16x16x32_bf16 v[120:123], v[162:165], v[178:181], v[120:123]
	v_mfma_f32_16x16x32_bf16 v[124:127], v[214:217], v[178:181], v[124:127]
	v_mfma_f32_16x16x32_bf16 v[68:71], v[218:221], v[178:181], v[68:71]
	s_waitcnt lgkmcnt(1)
	v_mfma_f32_16x16x32_bf16 v[128:131], v[158:161], v[222:225], v[128:131]
	v_mfma_f32_16x16x32_bf16 v[132:135], v[162:165], v[222:225], v[132:135]
	v_mfma_f32_16x16x32_bf16 v[136:139], v[214:217], v[222:225], v[136:139]
	v_mfma_f32_16x16x32_bf16 v[84:87], v[218:221], v[222:225], v[84:87]
	s_waitcnt lgkmcnt(0)
	v_mfma_f32_16x16x32_bf16 v[100:103], v[158:161], v[226:229], v[100:103]
	v_mfma_f32_16x16x32_bf16 v[140:143], v[162:165], v[226:229], v[140:143]
	v_mfma_f32_16x16x32_bf16 v[150:153], v[214:217], v[226:229], v[150:153]
	v_mfma_f32_16x16x32_bf16 v[154:157], v[218:221], v[226:229], v[154:157]
	s_add_u32 s50, s14, 0x500
	s_addc_u32 s51, s15, 0
	s_add_u32 s52, s20, 0x500
	s_waitcnt vmcnt(0)
	s_barrier
	s_addc_u32 s53, s21, 0
	ds_read_b128 v[158:161], v8
	ds_read_b128 v[162:165], v12
	ds_read_b128 v[166:169], v9
	ds_read_b128 v[178:181], v13
	ds_read_b128 v[214:217], v11
	ds_read_b128 v[218:221], v10
	ds_read_b128 v[222:225], v14
	ds_read_b128 v[226:229], v15
	s_waitcnt lgkmcnt(6)
	v_mfma_f32_16x16x32_bf16 v[40:43], v[158:161], v[162:165], v[40:43]
	s_waitcnt lgkmcnt(5)
	v_mfma_f32_16x16x32_bf16 v[44:47], v[166:169], v[162:165], v[44:47]
	s_waitcnt lgkmcnt(4)
	v_mfma_f32_16x16x32_bf16 v[56:59], v[158:161], v[178:181], v[56:59]
	s_mov_b32 m0, s1
	v_mfma_f32_16x16x32_bf16 v[60:63], v[166:169], v[178:181], v[60:63]
	global_load_lds_dwordx4 v0, s[50:51]
	s_waitcnt lgkmcnt(3)
	v_mfma_f32_16x16x32_bf16 v[48:51], v[214:217], v[162:165], v[48:51]
	v_mfma_f32_16x16x32_bf16 v[64:67], v[214:217], v[178:181], v[64:67]
	s_waitcnt lgkmcnt(2)
	v_mfma_f32_16x16x32_bf16 v[174:177], v[218:221], v[162:165], v[174:177]
	ds_read_b128 v[162:165], v16
	v_mfma_f32_16x16x32_bf16 v[170:173], v[218:221], v[178:181], v[170:173]
	ds_read_b128 v[178:181], v17
	s_waitcnt lgkmcnt(3)
	s_mov_b32 m0, s34
	v_mfma_f32_16x16x32_bf16 v[72:75], v[158:161], v[222:225], v[72:75]
	global_load_lds_dwordx4 v0, s[52:53]
	v_mfma_f32_16x16x32_bf16 v[76:79], v[166:169], v[222:225], v[76:79]
	v_mfma_f32_16x16x32_bf16 v[80:83], v[214:217], v[222:225], v[80:83]
	v_mfma_f32_16x16x32_bf16 v[32:35], v[218:221], v[222:225], v[32:35]
	ds_read_b128 v[222:225], v18
	s_waitcnt lgkmcnt(3)
	v_mfma_f32_16x16x32_bf16 v[88:91], v[158:161], v[226:229], v[88:91]
	s_mov_b32 m0, s35
	v_mfma_f32_16x16x32_bf16 v[92:95], v[166:169], v[226:229], v[92:95]
	global_load_lds_dwordx4 v2, s[50:51]
	v_mfma_f32_16x16x32_bf16 v[96:99], v[214:217], v[226:229], v[96:99]
	v_mfma_f32_16x16x32_bf16 v[36:39], v[218:221], v[226:229], v[36:39]
	ds_read_b128 v[226:229], v19
	s_waitcnt lgkmcnt(3)
	v_mfma_f32_16x16x32_bf16 v[104:107], v[158:161], v[162:165], v[104:107]
	s_waitcnt lgkmcnt(2)
	v_mfma_f32_16x16x32_bf16 v[116:119], v[158:161], v[178:181], v[116:119]
	s_waitcnt lgkmcnt(1)
	s_mov_b32 m0, s36
	v_mfma_f32_16x16x32_bf16 v[128:131], v[158:161], v[222:225], v[128:131]
	global_load_lds_dwordx4 v2, s[52:53]
	s_waitcnt lgkmcnt(0)
	v_mfma_f32_16x16x32_bf16 v[100:103], v[158:161], v[226:229], v[100:103]
	ds_read_b128 v[158:161], v20
	v_mfma_f32_16x16x32_bf16 v[108:111], v[166:169], v[162:165], v[108:111]
	v_mfma_f32_16x16x32_bf16 v[120:123], v[166:169], v[178:181], v[120:123]
	v_mfma_f32_16x16x32_bf16 v[132:135], v[166:169], v[222:225], v[132:135]
	s_mov_b32 m0, s37
	v_mfma_f32_16x16x32_bf16 v[140:143], v[166:169], v[226:229], v[140:143]
	global_load_lds_dwordx4 v4, s[50:51]
	ds_read_b128 v[166:169], v24
	v_mfma_f32_16x16x32_bf16 v[112:115], v[214:217], v[162:165], v[112:115]
	v_mfma_f32_16x16x32_bf16 v[52:55], v[218:221], v[162:165], v[52:55]
	ds_read_b128 v[162:165], v21
	v_mfma_f32_16x16x32_bf16 v[124:127], v[214:217], v[178:181], v[124:127]
	v_mfma_f32_16x16x32_bf16 v[68:71], v[218:221], v[178:181], v[68:71]
	ds_read_b128 v[178:181], v25
	s_mov_b32 m0, s38
	v_mfma_f32_16x16x32_bf16 v[136:139], v[214:217], v[222:225], v[136:139]
	global_load_lds_dwordx4 v4, s[52:53]
	v_mfma_f32_16x16x32_bf16 v[84:87], v[218:221], v[222:225], v[84:87]
	ds_read_b128 v[222:225], v26
	v_mfma_f32_16x16x32_bf16 v[150:153], v[214:217], v[226:229], v[150:153]
	ds_read_b128 v[214:217], v23
	v_mfma_f32_16x16x32_bf16 v[154:157], v[218:221], v[226:229], v[154:157]
	ds_read_b128 v[218:221], v22
	ds_read_b128 v[226:229], v27
	s_waitcnt lgkmcnt(6)
	v_mfma_f32_16x16x32_bf16 v[40:43], v[158:161], v[166:169], v[40:43]
	s_waitcnt lgkmcnt(5)
	s_mov_b32 m0, s39
	v_mfma_f32_16x16x32_bf16 v[44:47], v[162:165], v[166:169], v[44:47]
	global_load_lds_dwordx4 v146, s[50:51]
	s_waitcnt lgkmcnt(4)
	v_mfma_f32_16x16x32_bf16 v[56:59], v[158:161], v[178:181], v[56:59]
	v_mfma_f32_16x16x32_bf16 v[60:63], v[162:165], v[178:181], v[60:63]
	s_waitcnt lgkmcnt(3)
	v_mfma_f32_16x16x32_bf16 v[72:75], v[158:161], v[222:225], v[72:75]
	v_mfma_f32_16x16x32_bf16 v[76:79], v[162:165], v[222:225], v[76:79]
	s_waitcnt lgkmcnt(2)
	s_mov_b32 m0, s40
	v_mfma_f32_16x16x32_bf16 v[48:51], v[214:217], v[166:169], v[48:51]
	global_load_lds_dwordx4 v146, s[52:53]
	s_waitcnt lgkmcnt(1)
	v_mfma_f32_16x16x32_bf16 v[174:177], v[218:221], v[166:169], v[174:177]
	ds_read_b128 v[166:169], v28
	v_mfma_f32_16x16x32_bf16 v[64:67], v[214:217], v[178:181], v[64:67]
	v_mfma_f32_16x16x32_bf16 v[170:173], v[218:221], v[178:181], v[170:173]
	ds_read_b128 v[178:181], v29
	v_mfma_f32_16x16x32_bf16 v[80:83], v[214:217], v[222:225], v[80:83]
	v_mfma_f32_16x16x32_bf16 v[32:35], v[218:221], v[222:225], v[32:35]
	ds_read_b128 v[222:225], v30
	s_waitcnt lgkmcnt(3)
	v_mfma_f32_16x16x32_bf16 v[88:91], v[158:161], v[226:229], v[88:91]
	v_mfma_f32_16x16x32_bf16 v[92:95], v[162:165], v[226:229], v[92:95]
	v_mfma_f32_16x16x32_bf16 v[96:99], v[214:217], v[226:229], v[96:99]
	v_mfma_f32_16x16x32_bf16 v[36:39], v[218:221], v[226:229], v[36:39]
	ds_read_b128 v[226:229], v31
	s_waitcnt lgkmcnt(3)
	v_mfma_f32_16x16x32_bf16 v[104:107], v[158:161], v[166:169], v[104:107]
	v_mfma_f32_16x16x32_bf16 v[108:111], v[162:165], v[166:169], v[108:111]
	v_mfma_f32_16x16x32_bf16 v[112:115], v[214:217], v[166:169], v[112:115]
	v_mfma_f32_16x16x32_bf16 v[52:55], v[218:221], v[166:169], v[52:55]
	s_waitcnt lgkmcnt(2)
	v_mfma_f32_16x16x32_bf16 v[116:119], v[158:161], v[178:181], v[116:119]
	v_mfma_f32_16x16x32_bf16 v[120:123], v[162:165], v[178:181], v[120:123]
	v_mfma_f32_16x16x32_bf16 v[124:127], v[214:217], v[178:181], v[124:127]
	v_mfma_f32_16x16x32_bf16 v[68:71], v[218:221], v[178:181], v[68:71]
	s_waitcnt lgkmcnt(1)
	v_mfma_f32_16x16x32_bf16 v[128:131], v[158:161], v[222:225], v[128:131]
	v_mfma_f32_16x16x32_bf16 v[132:135], v[162:165], v[222:225], v[132:135]
	v_mfma_f32_16x16x32_bf16 v[136:139], v[214:217], v[222:225], v[136:139]
	v_mfma_f32_16x16x32_bf16 v[84:87], v[218:221], v[222:225], v[84:87]
	s_waitcnt lgkmcnt(0)
	v_mfma_f32_16x16x32_bf16 v[100:103], v[158:161], v[226:229], v[100:103]
	v_mfma_f32_16x16x32_bf16 v[140:143], v[162:165], v[226:229], v[140:143]
	v_mfma_f32_16x16x32_bf16 v[150:153], v[214:217], v[226:229], v[150:153]
	v_mfma_f32_16x16x32_bf16 v[154:157], v[218:221], v[226:229], v[154:157]
	s_add_u32 s50, s14, 0x580
	s_addc_u32 s51, s15, 0
	s_add_u32 s52, s20, 0x580
	s_waitcnt vmcnt(0)
	s_barrier
	s_addc_u32 s53, s21, 0
	ds_read_b128 v[158:161], v7 offset:32768
	ds_read_b128 v[162:165], v6
	ds_read_b128 v[166:169], v7 offset:34816
	ds_read_b128 v[178:181], v6 offset:2048
	ds_read_b128 v[214:217], v7 offset:36864
	ds_read_b128 v[218:221], v7 offset:38912
	ds_read_b128 v[222:225], v6 offset:4096
	ds_read_b128 v[226:229], v6 offset:6144
	s_waitcnt lgkmcnt(6)
	v_mfma_f32_16x16x32_bf16 v[40:43], v[158:161], v[162:165], v[40:43]
	s_waitcnt lgkmcnt(5)
	v_mfma_f32_16x16x32_bf16 v[44:47], v[166:169], v[162:165], v[44:47]
	s_waitcnt lgkmcnt(4)
	v_mfma_f32_16x16x32_bf16 v[56:59], v[158:161], v[178:181], v[56:59]
	s_mov_b32 m0, s27
	v_mfma_f32_16x16x32_bf16 v[60:63], v[166:169], v[178:181], v[60:63]
	global_load_lds_dwordx4 v0, s[50:51]
	s_waitcnt lgkmcnt(3)
	v_mfma_f32_16x16x32_bf16 v[48:51], v[214:217], v[162:165], v[48:51]
	v_mfma_f32_16x16x32_bf16 v[64:67], v[214:217], v[178:181], v[64:67]
	s_waitcnt lgkmcnt(2)
	v_mfma_f32_16x16x32_bf16 v[174:177], v[218:221], v[162:165], v[174:177]
	ds_read_b128 v[162:165], v6 offset:8192
	v_mfma_f32_16x16x32_bf16 v[170:173], v[218:221], v[178:181], v[170:173]
	ds_read_b128 v[178:181], v6 offset:10240
	s_waitcnt lgkmcnt(3)
	s_mov_b32 m0, s26
	v_mfma_f32_16x16x32_bf16 v[72:75], v[158:161], v[222:225], v[72:75]
	global_load_lds_dwordx4 v0, s[52:53]
	v_mfma_f32_16x16x32_bf16 v[76:79], v[166:169], v[222:225], v[76:79]
	v_mfma_f32_16x16x32_bf16 v[80:83], v[214:217], v[222:225], v[80:83]
	v_mfma_f32_16x16x32_bf16 v[32:35], v[218:221], v[222:225], v[32:35]
	ds_read_b128 v[222:225], v6 offset:12288
	s_waitcnt lgkmcnt(3)
	v_mfma_f32_16x16x32_bf16 v[88:91], v[158:161], v[226:229], v[88:91]
	s_mov_b32 m0, s41
	v_mfma_f32_16x16x32_bf16 v[92:95], v[166:169], v[226:229], v[92:95]
	global_load_lds_dwordx4 v2, s[50:51]
	v_mfma_f32_16x16x32_bf16 v[96:99], v[214:217], v[226:229], v[96:99]
	v_mfma_f32_16x16x32_bf16 v[36:39], v[218:221], v[226:229], v[36:39]
	ds_read_b128 v[226:229], v6 offset:14336
	s_waitcnt lgkmcnt(3)
	v_mfma_f32_16x16x32_bf16 v[104:107], v[158:161], v[162:165], v[104:107]
	s_waitcnt lgkmcnt(2)
	v_mfma_f32_16x16x32_bf16 v[116:119], v[158:161], v[178:181], v[116:119]
	s_waitcnt lgkmcnt(1)
	s_mov_b32 m0, s42
	v_mfma_f32_16x16x32_bf16 v[128:131], v[158:161], v[222:225], v[128:131]
	global_load_lds_dwordx4 v2, s[52:53]
	s_waitcnt lgkmcnt(0)
	v_mfma_f32_16x16x32_bf16 v[100:103], v[158:161], v[226:229], v[100:103]
	ds_read_b128 v[158:161], v7 offset:33792
	v_mfma_f32_16x16x32_bf16 v[108:111], v[166:169], v[162:165], v[108:111]
	v_mfma_f32_16x16x32_bf16 v[120:123], v[166:169], v[178:181], v[120:123]
	v_mfma_f32_16x16x32_bf16 v[132:135], v[166:169], v[222:225], v[132:135]
	s_mov_b32 m0, s43
	v_mfma_f32_16x16x32_bf16 v[140:143], v[166:169], v[226:229], v[140:143]
	global_load_lds_dwordx4 v4, s[50:51]
	ds_read_b128 v[166:169], v6 offset:1024
	v_mfma_f32_16x16x32_bf16 v[112:115], v[214:217], v[162:165], v[112:115]
	v_mfma_f32_16x16x32_bf16 v[52:55], v[218:221], v[162:165], v[52:55]
	ds_read_b128 v[162:165], v7 offset:35840
	v_mfma_f32_16x16x32_bf16 v[124:127], v[214:217], v[178:181], v[124:127]
	v_mfma_f32_16x16x32_bf16 v[68:71], v[218:221], v[178:181], v[68:71]
	ds_read_b128 v[178:181], v6 offset:3072
	s_mov_b32 m0, s44
	v_mfma_f32_16x16x32_bf16 v[136:139], v[214:217], v[222:225], v[136:139]
	global_load_lds_dwordx4 v4, s[52:53]
	v_mfma_f32_16x16x32_bf16 v[84:87], v[218:221], v[222:225], v[84:87]
	ds_read_b128 v[222:225], v6 offset:5120
	v_mfma_f32_16x16x32_bf16 v[150:153], v[214:217], v[226:229], v[150:153]
	ds_read_b128 v[214:217], v7 offset:37888
	v_mfma_f32_16x16x32_bf16 v[154:157], v[218:221], v[226:229], v[154:157]
	ds_read_b128 v[218:221], v7 offset:39936
	ds_read_b128 v[226:229], v6 offset:7168
	s_waitcnt lgkmcnt(6)
	v_mfma_f32_16x16x32_bf16 v[40:43], v[158:161], v[166:169], v[40:43]
	s_waitcnt lgkmcnt(5)
	s_mov_b32 m0, s45
	v_mfma_f32_16x16x32_bf16 v[44:47], v[162:165], v[166:169], v[44:47]
	global_load_lds_dwordx4 v146, s[50:51]
	s_waitcnt lgkmcnt(4)
	v_mfma_f32_16x16x32_bf16 v[56:59], v[158:161], v[178:181], v[56:59]
	v_mfma_f32_16x16x32_bf16 v[60:63], v[162:165], v[178:181], v[60:63]
	s_waitcnt lgkmcnt(3)
	v_mfma_f32_16x16x32_bf16 v[72:75], v[158:161], v[222:225], v[72:75]
	v_mfma_f32_16x16x32_bf16 v[76:79], v[162:165], v[222:225], v[76:79]
	s_waitcnt lgkmcnt(2)
	s_mov_b32 m0, s46
	v_mfma_f32_16x16x32_bf16 v[48:51], v[214:217], v[166:169], v[48:51]
	global_load_lds_dwordx4 v146, s[52:53]
	s_waitcnt lgkmcnt(1)
	v_mfma_f32_16x16x32_bf16 v[174:177], v[218:221], v[166:169], v[174:177]
	ds_read_b128 v[166:169], v6 offset:9216
	v_mfma_f32_16x16x32_bf16 v[64:67], v[214:217], v[178:181], v[64:67]
	v_mfma_f32_16x16x32_bf16 v[170:173], v[218:221], v[178:181], v[170:173]
	ds_read_b128 v[178:181], v6 offset:11264
	v_mfma_f32_16x16x32_bf16 v[80:83], v[214:217], v[222:225], v[80:83]
	v_mfma_f32_16x16x32_bf16 v[32:35], v[218:221], v[222:225], v[32:35]
	ds_read_b128 v[222:225], v6 offset:13312
	s_waitcnt lgkmcnt(3)
	v_mfma_f32_16x16x32_bf16 v[88:91], v[158:161], v[226:229], v[88:91]
	v_mfma_f32_16x16x32_bf16 v[92:95], v[162:165], v[226:229], v[92:95]
	v_mfma_f32_16x16x32_bf16 v[96:99], v[214:217], v[226:229], v[96:99]
	v_mfma_f32_16x16x32_bf16 v[36:39], v[218:221], v[226:229], v[36:39]
	ds_read_b128 v[226:229], v6 offset:15360
	s_waitcnt lgkmcnt(3)
	v_mfma_f32_16x16x32_bf16 v[104:107], v[158:161], v[166:169], v[104:107]
	v_mfma_f32_16x16x32_bf16 v[108:111], v[162:165], v[166:169], v[108:111]
	v_mfma_f32_16x16x32_bf16 v[112:115], v[214:217], v[166:169], v[112:115]
	v_mfma_f32_16x16x32_bf16 v[52:55], v[218:221], v[166:169], v[52:55]
	s_waitcnt lgkmcnt(2)
	v_mfma_f32_16x16x32_bf16 v[116:119], v[158:161], v[178:181], v[116:119]
	v_mfma_f32_16x16x32_bf16 v[120:123], v[162:165], v[178:181], v[120:123]
	v_mfma_f32_16x16x32_bf16 v[124:127], v[214:217], v[178:181], v[124:127]
	v_mfma_f32_16x16x32_bf16 v[68:71], v[218:221], v[178:181], v[68:71]
	s_waitcnt lgkmcnt(1)
	v_mfma_f32_16x16x32_bf16 v[128:131], v[158:161], v[222:225], v[128:131]
	v_mfma_f32_16x16x32_bf16 v[132:135], v[162:165], v[222:225], v[132:135]
	v_mfma_f32_16x16x32_bf16 v[136:139], v[214:217], v[222:225], v[136:139]
	v_mfma_f32_16x16x32_bf16 v[84:87], v[218:221], v[222:225], v[84:87]
	s_waitcnt lgkmcnt(0)
	v_mfma_f32_16x16x32_bf16 v[100:103], v[158:161], v[226:229], v[100:103]
	v_mfma_f32_16x16x32_bf16 v[140:143], v[162:165], v[226:229], v[140:143]
	v_mfma_f32_16x16x32_bf16 v[150:153], v[214:217], v[226:229], v[150:153]
	v_mfma_f32_16x16x32_bf16 v[154:157], v[218:221], v[226:229], v[154:157]
	s_add_u32 s50, s14, 0x600
	s_addc_u32 s51, s15, 0
	s_add_u32 s52, s20, 0x600
	s_waitcnt vmcnt(0)
	s_barrier
	s_addc_u32 s53, s21, 0
	ds_read_b128 v[158:161], v8
	ds_read_b128 v[162:165], v12
	ds_read_b128 v[166:169], v9
	ds_read_b128 v[178:181], v13
	ds_read_b128 v[214:217], v11
	ds_read_b128 v[218:221], v10
	ds_read_b128 v[222:225], v14
	ds_read_b128 v[226:229], v15
	s_waitcnt lgkmcnt(6)
	v_mfma_f32_16x16x32_bf16 v[40:43], v[158:161], v[162:165], v[40:43]
	s_waitcnt lgkmcnt(5)
	v_mfma_f32_16x16x32_bf16 v[44:47], v[166:169], v[162:165], v[44:47]
	s_waitcnt lgkmcnt(4)
	v_mfma_f32_16x16x32_bf16 v[56:59], v[158:161], v[178:181], v[56:59]
	s_mov_b32 m0, s1
	v_mfma_f32_16x16x32_bf16 v[60:63], v[166:169], v[178:181], v[60:63]
	global_load_lds_dwordx4 v0, s[50:51]
	s_waitcnt lgkmcnt(3)
	v_mfma_f32_16x16x32_bf16 v[48:51], v[214:217], v[162:165], v[48:51]
	v_mfma_f32_16x16x32_bf16 v[64:67], v[214:217], v[178:181], v[64:67]
	s_waitcnt lgkmcnt(2)
	v_mfma_f32_16x16x32_bf16 v[174:177], v[218:221], v[162:165], v[174:177]
	ds_read_b128 v[162:165], v16
	v_mfma_f32_16x16x32_bf16 v[170:173], v[218:221], v[178:181], v[170:173]
	ds_read_b128 v[178:181], v17
	s_waitcnt lgkmcnt(3)
	s_mov_b32 m0, s34
	v_mfma_f32_16x16x32_bf16 v[72:75], v[158:161], v[222:225], v[72:75]
	global_load_lds_dwordx4 v0, s[52:53]
	v_mfma_f32_16x16x32_bf16 v[76:79], v[166:169], v[222:225], v[76:79]
	v_mfma_f32_16x16x32_bf16 v[80:83], v[214:217], v[222:225], v[80:83]
	v_mfma_f32_16x16x32_bf16 v[32:35], v[218:221], v[222:225], v[32:35]
	ds_read_b128 v[222:225], v18
	s_waitcnt lgkmcnt(3)
	v_mfma_f32_16x16x32_bf16 v[88:91], v[158:161], v[226:229], v[88:91]
	s_mov_b32 m0, s35
	v_mfma_f32_16x16x32_bf16 v[92:95], v[166:169], v[226:229], v[92:95]
	global_load_lds_dwordx4 v2, s[50:51]
	v_mfma_f32_16x16x32_bf16 v[96:99], v[214:217], v[226:229], v[96:99]
	v_mfma_f32_16x16x32_bf16 v[36:39], v[218:221], v[226:229], v[36:39]
	ds_read_b128 v[226:229], v19
	s_waitcnt lgkmcnt(3)
	v_mfma_f32_16x16x32_bf16 v[104:107], v[158:161], v[162:165], v[104:107]
	s_waitcnt lgkmcnt(2)
	v_mfma_f32_16x16x32_bf16 v[116:119], v[158:161], v[178:181], v[116:119]
	s_waitcnt lgkmcnt(1)
	s_mov_b32 m0, s36
	v_mfma_f32_16x16x32_bf16 v[128:131], v[158:161], v[222:225], v[128:131]
	global_load_lds_dwordx4 v2, s[52:53]
	s_waitcnt lgkmcnt(0)
	v_mfma_f32_16x16x32_bf16 v[100:103], v[158:161], v[226:229], v[100:103]
	ds_read_b128 v[158:161], v20
	v_mfma_f32_16x16x32_bf16 v[108:111], v[166:169], v[162:165], v[108:111]
	v_mfma_f32_16x16x32_bf16 v[120:123], v[166:169], v[178:181], v[120:123]
	v_mfma_f32_16x16x32_bf16 v[132:135], v[166:169], v[222:225], v[132:135]
	s_mov_b32 m0, s37
	v_mfma_f32_16x16x32_bf16 v[140:143], v[166:169], v[226:229], v[140:143]
	global_load_lds_dwordx4 v4, s[50:51]
	ds_read_b128 v[166:169], v24
	v_mfma_f32_16x16x32_bf16 v[112:115], v[214:217], v[162:165], v[112:115]
	v_mfma_f32_16x16x32_bf16 v[52:55], v[218:221], v[162:165], v[52:55]
	ds_read_b128 v[162:165], v21
	v_mfma_f32_16x16x32_bf16 v[124:127], v[214:217], v[178:181], v[124:127]
	v_mfma_f32_16x16x32_bf16 v[68:71], v[218:221], v[178:181], v[68:71]
	ds_read_b128 v[178:181], v25
	s_mov_b32 m0, s38
	v_mfma_f32_16x16x32_bf16 v[136:139], v[214:217], v[222:225], v[136:139]
	global_load_lds_dwordx4 v4, s[52:53]
	v_mfma_f32_16x16x32_bf16 v[84:87], v[218:221], v[222:225], v[84:87]
	ds_read_b128 v[222:225], v26
	v_mfma_f32_16x16x32_bf16 v[150:153], v[214:217], v[226:229], v[150:153]
	ds_read_b128 v[214:217], v23
	v_mfma_f32_16x16x32_bf16 v[154:157], v[218:221], v[226:229], v[154:157]
	ds_read_b128 v[218:221], v22
	ds_read_b128 v[226:229], v27
	s_waitcnt lgkmcnt(6)
	v_mfma_f32_16x16x32_bf16 v[40:43], v[158:161], v[166:169], v[40:43]
	s_waitcnt lgkmcnt(5)
	s_mov_b32 m0, s39
	v_mfma_f32_16x16x32_bf16 v[44:47], v[162:165], v[166:169], v[44:47]
	global_load_lds_dwordx4 v146, s[50:51]
	s_waitcnt lgkmcnt(4)
	v_mfma_f32_16x16x32_bf16 v[56:59], v[158:161], v[178:181], v[56:59]
	v_mfma_f32_16x16x32_bf16 v[60:63], v[162:165], v[178:181], v[60:63]
	s_waitcnt lgkmcnt(3)
	v_mfma_f32_16x16x32_bf16 v[72:75], v[158:161], v[222:225], v[72:75]
	v_mfma_f32_16x16x32_bf16 v[76:79], v[162:165], v[222:225], v[76:79]
	s_waitcnt lgkmcnt(2)
	s_mov_b32 m0, s40
	v_mfma_f32_16x16x32_bf16 v[48:51], v[214:217], v[166:169], v[48:51]
	global_load_lds_dwordx4 v146, s[52:53]
	s_waitcnt lgkmcnt(1)
	v_mfma_f32_16x16x32_bf16 v[174:177], v[218:221], v[166:169], v[174:177]
	ds_read_b128 v[166:169], v28
	v_mfma_f32_16x16x32_bf16 v[64:67], v[214:217], v[178:181], v[64:67]
	v_mfma_f32_16x16x32_bf16 v[170:173], v[218:221], v[178:181], v[170:173]
	ds_read_b128 v[178:181], v29
	v_mfma_f32_16x16x32_bf16 v[80:83], v[214:217], v[222:225], v[80:83]
	v_mfma_f32_16x16x32_bf16 v[32:35], v[218:221], v[222:225], v[32:35]
	ds_read_b128 v[222:225], v30
	s_waitcnt lgkmcnt(3)
	v_mfma_f32_16x16x32_bf16 v[88:91], v[158:161], v[226:229], v[88:91]
	v_mfma_f32_16x16x32_bf16 v[92:95], v[162:165], v[226:229], v[92:95]
	v_mfma_f32_16x16x32_bf16 v[96:99], v[214:217], v[226:229], v[96:99]
	v_mfma_f32_16x16x32_bf16 v[36:39], v[218:221], v[226:229], v[36:39]
	ds_read_b128 v[226:229], v31
	s_waitcnt lgkmcnt(3)
	v_mfma_f32_16x16x32_bf16 v[104:107], v[158:161], v[166:169], v[104:107]
	v_mfma_f32_16x16x32_bf16 v[108:111], v[162:165], v[166:169], v[108:111]
	v_mfma_f32_16x16x32_bf16 v[112:115], v[214:217], v[166:169], v[112:115]
	v_mfma_f32_16x16x32_bf16 v[52:55], v[218:221], v[166:169], v[52:55]
	s_waitcnt lgkmcnt(2)
	v_mfma_f32_16x16x32_bf16 v[116:119], v[158:161], v[178:181], v[116:119]
	v_mfma_f32_16x16x32_bf16 v[120:123], v[162:165], v[178:181], v[120:123]
	v_mfma_f32_16x16x32_bf16 v[124:127], v[214:217], v[178:181], v[124:127]
	v_mfma_f32_16x16x32_bf16 v[68:71], v[218:221], v[178:181], v[68:71]
	s_waitcnt lgkmcnt(1)
	v_mfma_f32_16x16x32_bf16 v[128:131], v[158:161], v[222:225], v[128:131]
	v_mfma_f32_16x16x32_bf16 v[132:135], v[162:165], v[222:225], v[132:135]
	v_mfma_f32_16x16x32_bf16 v[136:139], v[214:217], v[222:225], v[136:139]
	v_mfma_f32_16x16x32_bf16 v[84:87], v[218:221], v[222:225], v[84:87]
	s_waitcnt lgkmcnt(0)
	v_mfma_f32_16x16x32_bf16 v[100:103], v[158:161], v[226:229], v[100:103]
	v_mfma_f32_16x16x32_bf16 v[140:143], v[162:165], v[226:229], v[140:143]
	v_mfma_f32_16x16x32_bf16 v[150:153], v[214:217], v[226:229], v[150:153]
	v_mfma_f32_16x16x32_bf16 v[154:157], v[218:221], v[226:229], v[154:157]
	s_add_u32 s50, s14, 0x680
	s_addc_u32 s51, s15, 0
	s_add_u32 s52, s20, 0x680
	s_waitcnt vmcnt(0)
	s_barrier
	s_addc_u32 s53, s21, 0
	ds_read_b128 v[158:161], v7 offset:32768
	ds_read_b128 v[162:165], v6
	ds_read_b128 v[166:169], v7 offset:34816
	ds_read_b128 v[178:181], v6 offset:2048
	ds_read_b128 v[214:217], v7 offset:36864
	ds_read_b128 v[218:221], v7 offset:38912
	ds_read_b128 v[222:225], v6 offset:4096
	ds_read_b128 v[226:229], v6 offset:6144
	s_waitcnt lgkmcnt(6)
	v_mfma_f32_16x16x32_bf16 v[40:43], v[158:161], v[162:165], v[40:43]
	s_waitcnt lgkmcnt(5)
	v_mfma_f32_16x16x32_bf16 v[44:47], v[166:169], v[162:165], v[44:47]
	s_waitcnt lgkmcnt(4)
	v_mfma_f32_16x16x32_bf16 v[56:59], v[158:161], v[178:181], v[56:59]
	s_mov_b32 m0, s27
	v_mfma_f32_16x16x32_bf16 v[60:63], v[166:169], v[178:181], v[60:63]
	global_load_lds_dwordx4 v0, s[50:51]
	s_waitcnt lgkmcnt(3)
	v_mfma_f32_16x16x32_bf16 v[48:51], v[214:217], v[162:165], v[48:51]
	v_mfma_f32_16x16x32_bf16 v[64:67], v[214:217], v[178:181], v[64:67]
	s_waitcnt lgkmcnt(2)
	v_mfma_f32_16x16x32_bf16 v[174:177], v[218:221], v[162:165], v[174:177]
	ds_read_b128 v[162:165], v6 offset:8192
	v_mfma_f32_16x16x32_bf16 v[170:173], v[218:221], v[178:181], v[170:173]
	ds_read_b128 v[178:181], v6 offset:10240
	s_waitcnt lgkmcnt(3)
	s_mov_b32 m0, s26
	v_mfma_f32_16x16x32_bf16 v[72:75], v[158:161], v[222:225], v[72:75]
	global_load_lds_dwordx4 v0, s[52:53]
	v_mfma_f32_16x16x32_bf16 v[76:79], v[166:169], v[222:225], v[76:79]
	v_mfma_f32_16x16x32_bf16 v[80:83], v[214:217], v[222:225], v[80:83]
	v_mfma_f32_16x16x32_bf16 v[32:35], v[218:221], v[222:225], v[32:35]
	ds_read_b128 v[222:225], v6 offset:12288
	s_waitcnt lgkmcnt(3)
	v_mfma_f32_16x16x32_bf16 v[88:91], v[158:161], v[226:229], v[88:91]
	s_mov_b32 m0, s41
	v_mfma_f32_16x16x32_bf16 v[92:95], v[166:169], v[226:229], v[92:95]
	global_load_lds_dwordx4 v2, s[50:51]
	v_mfma_f32_16x16x32_bf16 v[96:99], v[214:217], v[226:229], v[96:99]
	v_mfma_f32_16x16x32_bf16 v[36:39], v[218:221], v[226:229], v[36:39]
	ds_read_b128 v[226:229], v6 offset:14336
	s_waitcnt lgkmcnt(3)
	v_mfma_f32_16x16x32_bf16 v[104:107], v[158:161], v[162:165], v[104:107]
	s_waitcnt lgkmcnt(2)
	v_mfma_f32_16x16x32_bf16 v[116:119], v[158:161], v[178:181], v[116:119]
	s_waitcnt lgkmcnt(1)
	s_mov_b32 m0, s42
	v_mfma_f32_16x16x32_bf16 v[128:131], v[158:161], v[222:225], v[128:131]
	global_load_lds_dwordx4 v2, s[52:53]
	s_waitcnt lgkmcnt(0)
	v_mfma_f32_16x16x32_bf16 v[100:103], v[158:161], v[226:229], v[100:103]
	ds_read_b128 v[158:161], v7 offset:33792
	v_mfma_f32_16x16x32_bf16 v[108:111], v[166:169], v[162:165], v[108:111]
	v_mfma_f32_16x16x32_bf16 v[120:123], v[166:169], v[178:181], v[120:123]
	v_mfma_f32_16x16x32_bf16 v[132:135], v[166:169], v[222:225], v[132:135]
	s_mov_b32 m0, s43
	v_mfma_f32_16x16x32_bf16 v[140:143], v[166:169], v[226:229], v[140:143]
	global_load_lds_dwordx4 v4, s[50:51]
	ds_read_b128 v[166:169], v6 offset:1024
	v_mfma_f32_16x16x32_bf16 v[112:115], v[214:217], v[162:165], v[112:115]
	v_mfma_f32_16x16x32_bf16 v[52:55], v[218:221], v[162:165], v[52:55]
	ds_read_b128 v[162:165], v7 offset:35840
	v_mfma_f32_16x16x32_bf16 v[124:127], v[214:217], v[178:181], v[124:127]
	v_mfma_f32_16x16x32_bf16 v[68:71], v[218:221], v[178:181], v[68:71]
	ds_read_b128 v[178:181], v6 offset:3072
	s_mov_b32 m0, s44
	v_mfma_f32_16x16x32_bf16 v[136:139], v[214:217], v[222:225], v[136:139]
	global_load_lds_dwordx4 v4, s[52:53]
	v_mfma_f32_16x16x32_bf16 v[84:87], v[218:221], v[222:225], v[84:87]
	ds_read_b128 v[222:225], v6 offset:5120
	v_mfma_f32_16x16x32_bf16 v[150:153], v[214:217], v[226:229], v[150:153]
	ds_read_b128 v[214:217], v7 offset:37888
	v_mfma_f32_16x16x32_bf16 v[154:157], v[218:221], v[226:229], v[154:157]
	ds_read_b128 v[218:221], v7 offset:39936
	ds_read_b128 v[226:229], v6 offset:7168
	s_waitcnt lgkmcnt(6)
	v_mfma_f32_16x16x32_bf16 v[40:43], v[158:161], v[166:169], v[40:43]
	s_waitcnt lgkmcnt(5)
	s_mov_b32 m0, s45
	v_mfma_f32_16x16x32_bf16 v[44:47], v[162:165], v[166:169], v[44:47]
	global_load_lds_dwordx4 v146, s[50:51]
	s_waitcnt lgkmcnt(4)
	v_mfma_f32_16x16x32_bf16 v[56:59], v[158:161], v[178:181], v[56:59]
	v_mfma_f32_16x16x32_bf16 v[60:63], v[162:165], v[178:181], v[60:63]
	s_waitcnt lgkmcnt(3)
	v_mfma_f32_16x16x32_bf16 v[72:75], v[158:161], v[222:225], v[72:75]
	v_mfma_f32_16x16x32_bf16 v[76:79], v[162:165], v[222:225], v[76:79]
	s_waitcnt lgkmcnt(2)
	s_mov_b32 m0, s46
	v_mfma_f32_16x16x32_bf16 v[48:51], v[214:217], v[166:169], v[48:51]
	global_load_lds_dwordx4 v146, s[52:53]
	s_waitcnt lgkmcnt(1)
	v_mfma_f32_16x16x32_bf16 v[174:177], v[218:221], v[166:169], v[174:177]
	ds_read_b128 v[166:169], v6 offset:9216
	v_mfma_f32_16x16x32_bf16 v[64:67], v[214:217], v[178:181], v[64:67]
	v_mfma_f32_16x16x32_bf16 v[170:173], v[218:221], v[178:181], v[170:173]
	ds_read_b128 v[178:181], v6 offset:11264
	v_mfma_f32_16x16x32_bf16 v[80:83], v[214:217], v[222:225], v[80:83]
	v_mfma_f32_16x16x32_bf16 v[32:35], v[218:221], v[222:225], v[32:35]
	ds_read_b128 v[222:225], v6 offset:13312
	s_waitcnt lgkmcnt(3)
	v_mfma_f32_16x16x32_bf16 v[88:91], v[158:161], v[226:229], v[88:91]
	v_mfma_f32_16x16x32_bf16 v[92:95], v[162:165], v[226:229], v[92:95]
	v_mfma_f32_16x16x32_bf16 v[96:99], v[214:217], v[226:229], v[96:99]
	v_mfma_f32_16x16x32_bf16 v[36:39], v[218:221], v[226:229], v[36:39]
	ds_read_b128 v[226:229], v6 offset:15360
	s_waitcnt lgkmcnt(3)
	v_mfma_f32_16x16x32_bf16 v[104:107], v[158:161], v[166:169], v[104:107]
	v_mfma_f32_16x16x32_bf16 v[108:111], v[162:165], v[166:169], v[108:111]
	v_mfma_f32_16x16x32_bf16 v[112:115], v[214:217], v[166:169], v[112:115]
	v_mfma_f32_16x16x32_bf16 v[52:55], v[218:221], v[166:169], v[52:55]
	s_waitcnt lgkmcnt(2)
	v_mfma_f32_16x16x32_bf16 v[116:119], v[158:161], v[178:181], v[116:119]
	v_mfma_f32_16x16x32_bf16 v[120:123], v[162:165], v[178:181], v[120:123]
	v_mfma_f32_16x16x32_bf16 v[124:127], v[214:217], v[178:181], v[124:127]
	v_mfma_f32_16x16x32_bf16 v[68:71], v[218:221], v[178:181], v[68:71]
	s_waitcnt lgkmcnt(1)
	v_mfma_f32_16x16x32_bf16 v[128:131], v[158:161], v[222:225], v[128:131]
	v_mfma_f32_16x16x32_bf16 v[132:135], v[162:165], v[222:225], v[132:135]
	v_mfma_f32_16x16x32_bf16 v[136:139], v[214:217], v[222:225], v[136:139]
	v_mfma_f32_16x16x32_bf16 v[84:87], v[218:221], v[222:225], v[84:87]
	s_waitcnt lgkmcnt(0)
	v_mfma_f32_16x16x32_bf16 v[100:103], v[158:161], v[226:229], v[100:103]
	v_mfma_f32_16x16x32_bf16 v[140:143], v[162:165], v[226:229], v[140:143]
	v_mfma_f32_16x16x32_bf16 v[150:153], v[214:217], v[226:229], v[150:153]
	v_mfma_f32_16x16x32_bf16 v[154:157], v[218:221], v[226:229], v[154:157]
	s_add_u32 s50, s14, 0x700
	s_addc_u32 s51, s15, 0
	s_add_u32 s52, s20, 0x700
	s_waitcnt vmcnt(0)
	s_barrier
	s_addc_u32 s53, s21, 0
	ds_read_b128 v[158:161], v8
	ds_read_b128 v[162:165], v12
	ds_read_b128 v[166:169], v9
	ds_read_b128 v[178:181], v13
	ds_read_b128 v[214:217], v11
	ds_read_b128 v[218:221], v10
	ds_read_b128 v[222:225], v14
	ds_read_b128 v[226:229], v15
	s_waitcnt lgkmcnt(6)
	v_mfma_f32_16x16x32_bf16 v[40:43], v[158:161], v[162:165], v[40:43]
	s_waitcnt lgkmcnt(5)
	v_mfma_f32_16x16x32_bf16 v[44:47], v[166:169], v[162:165], v[44:47]
	s_waitcnt lgkmcnt(4)
	v_mfma_f32_16x16x32_bf16 v[56:59], v[158:161], v[178:181], v[56:59]
	s_mov_b32 m0, s1
	v_mfma_f32_16x16x32_bf16 v[60:63], v[166:169], v[178:181], v[60:63]
	global_load_lds_dwordx4 v0, s[50:51]
	s_waitcnt lgkmcnt(3)
	v_mfma_f32_16x16x32_bf16 v[48:51], v[214:217], v[162:165], v[48:51]
	v_mfma_f32_16x16x32_bf16 v[64:67], v[214:217], v[178:181], v[64:67]
	s_waitcnt lgkmcnt(2)
	v_mfma_f32_16x16x32_bf16 v[174:177], v[218:221], v[162:165], v[174:177]
	ds_read_b128 v[162:165], v16
	v_mfma_f32_16x16x32_bf16 v[170:173], v[218:221], v[178:181], v[170:173]
	ds_read_b128 v[178:181], v17
	s_waitcnt lgkmcnt(3)
	s_mov_b32 m0, s34
	v_mfma_f32_16x16x32_bf16 v[72:75], v[158:161], v[222:225], v[72:75]
	global_load_lds_dwordx4 v0, s[52:53]
	v_mfma_f32_16x16x32_bf16 v[76:79], v[166:169], v[222:225], v[76:79]
	v_mfma_f32_16x16x32_bf16 v[80:83], v[214:217], v[222:225], v[80:83]
	v_mfma_f32_16x16x32_bf16 v[32:35], v[218:221], v[222:225], v[32:35]
	ds_read_b128 v[222:225], v18
	s_waitcnt lgkmcnt(3)
	v_mfma_f32_16x16x32_bf16 v[88:91], v[158:161], v[226:229], v[88:91]
	s_mov_b32 m0, s35
	v_mfma_f32_16x16x32_bf16 v[92:95], v[166:169], v[226:229], v[92:95]
	global_load_lds_dwordx4 v2, s[50:51]
	v_mfma_f32_16x16x32_bf16 v[96:99], v[214:217], v[226:229], v[96:99]
	v_mfma_f32_16x16x32_bf16 v[36:39], v[218:221], v[226:229], v[36:39]
	ds_read_b128 v[226:229], v19
	s_waitcnt lgkmcnt(3)
	v_mfma_f32_16x16x32_bf16 v[104:107], v[158:161], v[162:165], v[104:107]
	s_waitcnt lgkmcnt(2)
	v_mfma_f32_16x16x32_bf16 v[116:119], v[158:161], v[178:181], v[116:119]
	s_waitcnt lgkmcnt(1)
	s_mov_b32 m0, s36
	v_mfma_f32_16x16x32_bf16 v[128:131], v[158:161], v[222:225], v[128:131]
	global_load_lds_dwordx4 v2, s[52:53]
	s_waitcnt lgkmcnt(0)
	v_mfma_f32_16x16x32_bf16 v[100:103], v[158:161], v[226:229], v[100:103]
	ds_read_b128 v[158:161], v20
	v_mfma_f32_16x16x32_bf16 v[108:111], v[166:169], v[162:165], v[108:111]
	v_mfma_f32_16x16x32_bf16 v[120:123], v[166:169], v[178:181], v[120:123]
	v_mfma_f32_16x16x32_bf16 v[132:135], v[166:169], v[222:225], v[132:135]
	s_mov_b32 m0, s37
	v_mfma_f32_16x16x32_bf16 v[140:143], v[166:169], v[226:229], v[140:143]
	global_load_lds_dwordx4 v4, s[50:51]
	ds_read_b128 v[166:169], v24
	v_mfma_f32_16x16x32_bf16 v[112:115], v[214:217], v[162:165], v[112:115]
	v_mfma_f32_16x16x32_bf16 v[52:55], v[218:221], v[162:165], v[52:55]
	ds_read_b128 v[162:165], v21
	v_mfma_f32_16x16x32_bf16 v[124:127], v[214:217], v[178:181], v[124:127]
	v_mfma_f32_16x16x32_bf16 v[68:71], v[218:221], v[178:181], v[68:71]
	ds_read_b128 v[178:181], v25
	s_mov_b32 m0, s38
	v_mfma_f32_16x16x32_bf16 v[136:139], v[214:217], v[222:225], v[136:139]
	global_load_lds_dwordx4 v4, s[52:53]
	v_mfma_f32_16x16x32_bf16 v[84:87], v[218:221], v[222:225], v[84:87]
	ds_read_b128 v[222:225], v26
	v_mfma_f32_16x16x32_bf16 v[150:153], v[214:217], v[226:229], v[150:153]
	ds_read_b128 v[214:217], v23
	v_mfma_f32_16x16x32_bf16 v[154:157], v[218:221], v[226:229], v[154:157]
	ds_read_b128 v[218:221], v22
	ds_read_b128 v[226:229], v27
	s_waitcnt lgkmcnt(6)
	v_mfma_f32_16x16x32_bf16 v[40:43], v[158:161], v[166:169], v[40:43]
	s_waitcnt lgkmcnt(5)
	s_mov_b32 m0, s39
	v_mfma_f32_16x16x32_bf16 v[44:47], v[162:165], v[166:169], v[44:47]
	global_load_lds_dwordx4 v146, s[50:51]
	s_waitcnt lgkmcnt(4)
	v_mfma_f32_16x16x32_bf16 v[56:59], v[158:161], v[178:181], v[56:59]
	v_mfma_f32_16x16x32_bf16 v[60:63], v[162:165], v[178:181], v[60:63]
	s_waitcnt lgkmcnt(3)
	v_mfma_f32_16x16x32_bf16 v[72:75], v[158:161], v[222:225], v[72:75]
	v_mfma_f32_16x16x32_bf16 v[76:79], v[162:165], v[222:225], v[76:79]
	s_waitcnt lgkmcnt(2)
	s_mov_b32 m0, s40
	v_mfma_f32_16x16x32_bf16 v[48:51], v[214:217], v[166:169], v[48:51]
	global_load_lds_dwordx4 v146, s[52:53]
	s_waitcnt lgkmcnt(1)
	v_mfma_f32_16x16x32_bf16 v[174:177], v[218:221], v[166:169], v[174:177]
	ds_read_b128 v[166:169], v28
	v_mfma_f32_16x16x32_bf16 v[64:67], v[214:217], v[178:181], v[64:67]
	v_mfma_f32_16x16x32_bf16 v[170:173], v[218:221], v[178:181], v[170:173]
	ds_read_b128 v[178:181], v29
	v_mfma_f32_16x16x32_bf16 v[80:83], v[214:217], v[222:225], v[80:83]
	v_mfma_f32_16x16x32_bf16 v[32:35], v[218:221], v[222:225], v[32:35]
	ds_read_b128 v[222:225], v30
	s_waitcnt lgkmcnt(3)
	v_mfma_f32_16x16x32_bf16 v[88:91], v[158:161], v[226:229], v[88:91]
	v_mfma_f32_16x16x32_bf16 v[92:95], v[162:165], v[226:229], v[92:95]
	v_mfma_f32_16x16x32_bf16 v[96:99], v[214:217], v[226:229], v[96:99]
	v_mfma_f32_16x16x32_bf16 v[36:39], v[218:221], v[226:229], v[36:39]
	ds_read_b128 v[226:229], v31
	s_waitcnt lgkmcnt(3)
	v_mfma_f32_16x16x32_bf16 v[104:107], v[158:161], v[166:169], v[104:107]
	v_mfma_f32_16x16x32_bf16 v[108:111], v[162:165], v[166:169], v[108:111]
	v_mfma_f32_16x16x32_bf16 v[112:115], v[214:217], v[166:169], v[112:115]
	v_mfma_f32_16x16x32_bf16 v[52:55], v[218:221], v[166:169], v[52:55]
	s_waitcnt lgkmcnt(2)
	v_mfma_f32_16x16x32_bf16 v[116:119], v[158:161], v[178:181], v[116:119]
	v_mfma_f32_16x16x32_bf16 v[120:123], v[162:165], v[178:181], v[120:123]
	v_mfma_f32_16x16x32_bf16 v[124:127], v[214:217], v[178:181], v[124:127]
	v_mfma_f32_16x16x32_bf16 v[68:71], v[218:221], v[178:181], v[68:71]
	s_waitcnt lgkmcnt(1)
	v_mfma_f32_16x16x32_bf16 v[128:131], v[158:161], v[222:225], v[128:131]
	v_mfma_f32_16x16x32_bf16 v[132:135], v[162:165], v[222:225], v[132:135]
	v_mfma_f32_16x16x32_bf16 v[136:139], v[214:217], v[222:225], v[136:139]
	v_mfma_f32_16x16x32_bf16 v[84:87], v[218:221], v[222:225], v[84:87]
	s_waitcnt lgkmcnt(0)
	v_mfma_f32_16x16x32_bf16 v[100:103], v[158:161], v[226:229], v[100:103]
	v_mfma_f32_16x16x32_bf16 v[140:143], v[162:165], v[226:229], v[140:143]
	v_mfma_f32_16x16x32_bf16 v[150:153], v[214:217], v[226:229], v[150:153]
	v_mfma_f32_16x16x32_bf16 v[154:157], v[218:221], v[226:229], v[154:157]
	s_add_u32 s50, s14, 0x780
	s_addc_u32 s51, s15, 0
	s_add_u32 s52, s20, 0x780
	s_waitcnt vmcnt(0)
	s_barrier
	s_addc_u32 s53, s21, 0
	ds_read_b128 v[158:161], v7 offset:32768
	ds_read_b128 v[162:165], v6
	ds_read_b128 v[166:169], v7 offset:34816
	ds_read_b128 v[178:181], v6 offset:2048
	ds_read_b128 v[214:217], v7 offset:36864
	ds_read_b128 v[218:221], v7 offset:38912
	ds_read_b128 v[222:225], v6 offset:4096
	ds_read_b128 v[226:229], v6 offset:6144
	s_waitcnt lgkmcnt(6)
	v_mfma_f32_16x16x32_bf16 v[40:43], v[158:161], v[162:165], v[40:43]
	s_waitcnt lgkmcnt(5)
	v_mfma_f32_16x16x32_bf16 v[44:47], v[166:169], v[162:165], v[44:47]
	s_waitcnt lgkmcnt(4)
	v_mfma_f32_16x16x32_bf16 v[56:59], v[158:161], v[178:181], v[56:59]
	s_mov_b32 m0, s27
	v_mfma_f32_16x16x32_bf16 v[60:63], v[166:169], v[178:181], v[60:63]
	global_load_lds_dwordx4 v0, s[50:51]
	s_waitcnt lgkmcnt(3)
	v_mfma_f32_16x16x32_bf16 v[48:51], v[214:217], v[162:165], v[48:51]
	v_mfma_f32_16x16x32_bf16 v[64:67], v[214:217], v[178:181], v[64:67]
	s_waitcnt lgkmcnt(2)
	v_mfma_f32_16x16x32_bf16 v[174:177], v[218:221], v[162:165], v[174:177]
	ds_read_b128 v[162:165], v6 offset:8192
	v_mfma_f32_16x16x32_bf16 v[170:173], v[218:221], v[178:181], v[170:173]
	ds_read_b128 v[178:181], v6 offset:10240
	s_waitcnt lgkmcnt(3)
	s_mov_b32 m0, s26
	v_mfma_f32_16x16x32_bf16 v[72:75], v[158:161], v[222:225], v[72:75]
	global_load_lds_dwordx4 v0, s[52:53]
	v_mfma_f32_16x16x32_bf16 v[76:79], v[166:169], v[222:225], v[76:79]
	v_mfma_f32_16x16x32_bf16 v[80:83], v[214:217], v[222:225], v[80:83]
	v_mfma_f32_16x16x32_bf16 v[32:35], v[218:221], v[222:225], v[32:35]
	ds_read_b128 v[222:225], v6 offset:12288
	s_waitcnt lgkmcnt(3)
	v_mfma_f32_16x16x32_bf16 v[88:91], v[158:161], v[226:229], v[88:91]
	s_mov_b32 m0, s41
	v_mfma_f32_16x16x32_bf16 v[92:95], v[166:169], v[226:229], v[92:95]
	global_load_lds_dwordx4 v2, s[50:51]
	v_mfma_f32_16x16x32_bf16 v[96:99], v[214:217], v[226:229], v[96:99]
	v_mfma_f32_16x16x32_bf16 v[36:39], v[218:221], v[226:229], v[36:39]
	ds_read_b128 v[226:229], v6 offset:14336
	s_waitcnt lgkmcnt(3)
	v_mfma_f32_16x16x32_bf16 v[104:107], v[158:161], v[162:165], v[104:107]
	s_waitcnt lgkmcnt(2)
	v_mfma_f32_16x16x32_bf16 v[116:119], v[158:161], v[178:181], v[116:119]
	s_waitcnt lgkmcnt(1)
	s_mov_b32 m0, s42
	v_mfma_f32_16x16x32_bf16 v[128:131], v[158:161], v[222:225], v[128:131]
	global_load_lds_dwordx4 v2, s[52:53]
	s_waitcnt lgkmcnt(0)
	v_mfma_f32_16x16x32_bf16 v[100:103], v[158:161], v[226:229], v[100:103]
	ds_read_b128 v[158:161], v7 offset:33792
	v_mfma_f32_16x16x32_bf16 v[108:111], v[166:169], v[162:165], v[108:111]
	v_mfma_f32_16x16x32_bf16 v[120:123], v[166:169], v[178:181], v[120:123]
	v_mfma_f32_16x16x32_bf16 v[132:135], v[166:169], v[222:225], v[132:135]
	s_mov_b32 m0, s43
	v_mfma_f32_16x16x32_bf16 v[140:143], v[166:169], v[226:229], v[140:143]
	global_load_lds_dwordx4 v4, s[50:51]
	ds_read_b128 v[166:169], v6 offset:1024
	v_mfma_f32_16x16x32_bf16 v[112:115], v[214:217], v[162:165], v[112:115]
	v_mfma_f32_16x16x32_bf16 v[52:55], v[218:221], v[162:165], v[52:55]
	ds_read_b128 v[162:165], v7 offset:35840
	v_mfma_f32_16x16x32_bf16 v[124:127], v[214:217], v[178:181], v[124:127]
	v_mfma_f32_16x16x32_bf16 v[68:71], v[218:221], v[178:181], v[68:71]
	ds_read_b128 v[178:181], v6 offset:3072
	s_mov_b32 m0, s44
	v_mfma_f32_16x16x32_bf16 v[136:139], v[214:217], v[222:225], v[136:139]
	global_load_lds_dwordx4 v4, s[52:53]
	v_mfma_f32_16x16x32_bf16 v[84:87], v[218:221], v[222:225], v[84:87]
	ds_read_b128 v[222:225], v6 offset:5120
	v_mfma_f32_16x16x32_bf16 v[150:153], v[214:217], v[226:229], v[150:153]
	ds_read_b128 v[214:217], v7 offset:37888
	v_mfma_f32_16x16x32_bf16 v[154:157], v[218:221], v[226:229], v[154:157]
	ds_read_b128 v[218:221], v7 offset:39936
	ds_read_b128 v[226:229], v6 offset:7168
	s_waitcnt lgkmcnt(6)
	v_mfma_f32_16x16x32_bf16 v[40:43], v[158:161], v[166:169], v[40:43]
	s_waitcnt lgkmcnt(5)
	s_mov_b32 m0, s45
	v_mfma_f32_16x16x32_bf16 v[44:47], v[162:165], v[166:169], v[44:47]
	global_load_lds_dwordx4 v146, s[50:51]
	s_waitcnt lgkmcnt(4)
	v_mfma_f32_16x16x32_bf16 v[56:59], v[158:161], v[178:181], v[56:59]
	v_mfma_f32_16x16x32_bf16 v[60:63], v[162:165], v[178:181], v[60:63]
	s_waitcnt lgkmcnt(3)
	v_mfma_f32_16x16x32_bf16 v[72:75], v[158:161], v[222:225], v[72:75]
	v_mfma_f32_16x16x32_bf16 v[76:79], v[162:165], v[222:225], v[76:79]
	s_waitcnt lgkmcnt(2)
	s_mov_b32 m0, s46
	v_mfma_f32_16x16x32_bf16 v[48:51], v[214:217], v[166:169], v[48:51]
	global_load_lds_dwordx4 v146, s[52:53]
	s_waitcnt lgkmcnt(1)
	v_mfma_f32_16x16x32_bf16 v[174:177], v[218:221], v[166:169], v[174:177]
	ds_read_b128 v[166:169], v6 offset:9216
	v_mfma_f32_16x16x32_bf16 v[64:67], v[214:217], v[178:181], v[64:67]
	v_mfma_f32_16x16x32_bf16 v[170:173], v[218:221], v[178:181], v[170:173]
	ds_read_b128 v[178:181], v6 offset:11264
	v_mfma_f32_16x16x32_bf16 v[80:83], v[214:217], v[222:225], v[80:83]
	v_mfma_f32_16x16x32_bf16 v[32:35], v[218:221], v[222:225], v[32:35]
	ds_read_b128 v[222:225], v6 offset:13312
	s_waitcnt lgkmcnt(3)
	v_mfma_f32_16x16x32_bf16 v[88:91], v[158:161], v[226:229], v[88:91]
	v_mfma_f32_16x16x32_bf16 v[92:95], v[162:165], v[226:229], v[92:95]
	v_mfma_f32_16x16x32_bf16 v[96:99], v[214:217], v[226:229], v[96:99]
	v_mfma_f32_16x16x32_bf16 v[36:39], v[218:221], v[226:229], v[36:39]
	ds_read_b128 v[226:229], v6 offset:15360
	s_waitcnt lgkmcnt(3)
	v_mfma_f32_16x16x32_bf16 v[104:107], v[158:161], v[166:169], v[104:107]
	v_mfma_f32_16x16x32_bf16 v[108:111], v[162:165], v[166:169], v[108:111]
	v_mfma_f32_16x16x32_bf16 v[112:115], v[214:217], v[166:169], v[112:115]
	v_mfma_f32_16x16x32_bf16 v[52:55], v[218:221], v[166:169], v[52:55]
	s_waitcnt lgkmcnt(2)
	v_mfma_f32_16x16x32_bf16 v[116:119], v[158:161], v[178:181], v[116:119]
	v_mfma_f32_16x16x32_bf16 v[120:123], v[162:165], v[178:181], v[120:123]
	v_mfma_f32_16x16x32_bf16 v[124:127], v[214:217], v[178:181], v[124:127]
	v_mfma_f32_16x16x32_bf16 v[68:71], v[218:221], v[178:181], v[68:71]
	s_waitcnt lgkmcnt(1)
	v_mfma_f32_16x16x32_bf16 v[128:131], v[158:161], v[222:225], v[128:131]
	v_mfma_f32_16x16x32_bf16 v[132:135], v[162:165], v[222:225], v[132:135]
	v_mfma_f32_16x16x32_bf16 v[136:139], v[214:217], v[222:225], v[136:139]
	v_mfma_f32_16x16x32_bf16 v[84:87], v[218:221], v[222:225], v[84:87]
	s_waitcnt lgkmcnt(0)
	v_mfma_f32_16x16x32_bf16 v[100:103], v[158:161], v[226:229], v[100:103]
	v_mfma_f32_16x16x32_bf16 v[140:143], v[162:165], v[226:229], v[140:143]
	v_mfma_f32_16x16x32_bf16 v[150:153], v[214:217], v[226:229], v[150:153]
	v_mfma_f32_16x16x32_bf16 v[154:157], v[218:221], v[226:229], v[154:157]
	s_add_u32 s50, s14, 0x800
	s_addc_u32 s51, s15, 0
	s_add_u32 s52, s20, 0x800
	s_waitcnt vmcnt(0)
	s_barrier
	s_addc_u32 s53, s21, 0
	ds_read_b128 v[158:161], v8
	ds_read_b128 v[162:165], v12
	ds_read_b128 v[166:169], v9
	ds_read_b128 v[178:181], v13
	ds_read_b128 v[214:217], v11
	ds_read_b128 v[218:221], v10
	ds_read_b128 v[222:225], v14
	ds_read_b128 v[226:229], v15
	s_waitcnt lgkmcnt(6)
	v_mfma_f32_16x16x32_bf16 v[40:43], v[158:161], v[162:165], v[40:43]
	s_waitcnt lgkmcnt(5)
	v_mfma_f32_16x16x32_bf16 v[44:47], v[166:169], v[162:165], v[44:47]
	s_waitcnt lgkmcnt(4)
	v_mfma_f32_16x16x32_bf16 v[56:59], v[158:161], v[178:181], v[56:59]
	s_mov_b32 m0, s1
	v_mfma_f32_16x16x32_bf16 v[60:63], v[166:169], v[178:181], v[60:63]
	global_load_lds_dwordx4 v0, s[50:51]
	s_waitcnt lgkmcnt(3)
	v_mfma_f32_16x16x32_bf16 v[48:51], v[214:217], v[162:165], v[48:51]
	v_mfma_f32_16x16x32_bf16 v[64:67], v[214:217], v[178:181], v[64:67]
	s_waitcnt lgkmcnt(2)
	v_mfma_f32_16x16x32_bf16 v[174:177], v[218:221], v[162:165], v[174:177]
	ds_read_b128 v[162:165], v16
	v_mfma_f32_16x16x32_bf16 v[170:173], v[218:221], v[178:181], v[170:173]
	ds_read_b128 v[178:181], v17
	s_waitcnt lgkmcnt(3)
	s_mov_b32 m0, s34
	v_mfma_f32_16x16x32_bf16 v[72:75], v[158:161], v[222:225], v[72:75]
	global_load_lds_dwordx4 v0, s[52:53]
	v_mfma_f32_16x16x32_bf16 v[76:79], v[166:169], v[222:225], v[76:79]
	v_mfma_f32_16x16x32_bf16 v[80:83], v[214:217], v[222:225], v[80:83]
	v_mfma_f32_16x16x32_bf16 v[32:35], v[218:221], v[222:225], v[32:35]
	ds_read_b128 v[222:225], v18
	s_waitcnt lgkmcnt(3)
	v_mfma_f32_16x16x32_bf16 v[88:91], v[158:161], v[226:229], v[88:91]
	s_mov_b32 m0, s35
	v_mfma_f32_16x16x32_bf16 v[92:95], v[166:169], v[226:229], v[92:95]
	global_load_lds_dwordx4 v2, s[50:51]
	v_mfma_f32_16x16x32_bf16 v[96:99], v[214:217], v[226:229], v[96:99]
	v_mfma_f32_16x16x32_bf16 v[36:39], v[218:221], v[226:229], v[36:39]
	ds_read_b128 v[226:229], v19
	s_waitcnt lgkmcnt(3)
	v_mfma_f32_16x16x32_bf16 v[104:107], v[158:161], v[162:165], v[104:107]
	s_waitcnt lgkmcnt(2)
	v_mfma_f32_16x16x32_bf16 v[116:119], v[158:161], v[178:181], v[116:119]
	s_waitcnt lgkmcnt(1)
	s_mov_b32 m0, s36
	v_mfma_f32_16x16x32_bf16 v[128:131], v[158:161], v[222:225], v[128:131]
	global_load_lds_dwordx4 v2, s[52:53]
	s_waitcnt lgkmcnt(0)
	v_mfma_f32_16x16x32_bf16 v[100:103], v[158:161], v[226:229], v[100:103]
	ds_read_b128 v[158:161], v20
	v_mfma_f32_16x16x32_bf16 v[108:111], v[166:169], v[162:165], v[108:111]
	v_mfma_f32_16x16x32_bf16 v[120:123], v[166:169], v[178:181], v[120:123]
	v_mfma_f32_16x16x32_bf16 v[132:135], v[166:169], v[222:225], v[132:135]
	s_mov_b32 m0, s37
	v_mfma_f32_16x16x32_bf16 v[140:143], v[166:169], v[226:229], v[140:143]
	global_load_lds_dwordx4 v4, s[50:51]
	ds_read_b128 v[166:169], v24
	v_mfma_f32_16x16x32_bf16 v[112:115], v[214:217], v[162:165], v[112:115]
	v_mfma_f32_16x16x32_bf16 v[52:55], v[218:221], v[162:165], v[52:55]
	ds_read_b128 v[162:165], v21
	v_mfma_f32_16x16x32_bf16 v[124:127], v[214:217], v[178:181], v[124:127]
	v_mfma_f32_16x16x32_bf16 v[68:71], v[218:221], v[178:181], v[68:71]
	ds_read_b128 v[178:181], v25
	s_mov_b32 m0, s38
	v_mfma_f32_16x16x32_bf16 v[136:139], v[214:217], v[222:225], v[136:139]
	global_load_lds_dwordx4 v4, s[52:53]
	v_mfma_f32_16x16x32_bf16 v[84:87], v[218:221], v[222:225], v[84:87]
	ds_read_b128 v[222:225], v26
	v_mfma_f32_16x16x32_bf16 v[150:153], v[214:217], v[226:229], v[150:153]
	ds_read_b128 v[214:217], v23
	v_mfma_f32_16x16x32_bf16 v[154:157], v[218:221], v[226:229], v[154:157]
	ds_read_b128 v[218:221], v22
	ds_read_b128 v[226:229], v27
	s_waitcnt lgkmcnt(6)
	v_mfma_f32_16x16x32_bf16 v[40:43], v[158:161], v[166:169], v[40:43]
	s_waitcnt lgkmcnt(5)
	s_mov_b32 m0, s39
	v_mfma_f32_16x16x32_bf16 v[44:47], v[162:165], v[166:169], v[44:47]
	global_load_lds_dwordx4 v146, s[50:51]
	s_waitcnt lgkmcnt(4)
	v_mfma_f32_16x16x32_bf16 v[56:59], v[158:161], v[178:181], v[56:59]
	v_mfma_f32_16x16x32_bf16 v[60:63], v[162:165], v[178:181], v[60:63]
	s_waitcnt lgkmcnt(3)
	v_mfma_f32_16x16x32_bf16 v[72:75], v[158:161], v[222:225], v[72:75]
	v_mfma_f32_16x16x32_bf16 v[76:79], v[162:165], v[222:225], v[76:79]
	s_waitcnt lgkmcnt(2)
	s_mov_b32 m0, s40
	v_mfma_f32_16x16x32_bf16 v[48:51], v[214:217], v[166:169], v[48:51]
	global_load_lds_dwordx4 v146, s[52:53]
	s_waitcnt lgkmcnt(1)
	v_mfma_f32_16x16x32_bf16 v[174:177], v[218:221], v[166:169], v[174:177]
	ds_read_b128 v[166:169], v28
	v_mfma_f32_16x16x32_bf16 v[64:67], v[214:217], v[178:181], v[64:67]
	v_mfma_f32_16x16x32_bf16 v[170:173], v[218:221], v[178:181], v[170:173]
	ds_read_b128 v[178:181], v29
	v_mfma_f32_16x16x32_bf16 v[80:83], v[214:217], v[222:225], v[80:83]
	v_mfma_f32_16x16x32_bf16 v[32:35], v[218:221], v[222:225], v[32:35]
	ds_read_b128 v[222:225], v30
	s_waitcnt lgkmcnt(3)
	v_mfma_f32_16x16x32_bf16 v[88:91], v[158:161], v[226:229], v[88:91]
	v_mfma_f32_16x16x32_bf16 v[92:95], v[162:165], v[226:229], v[92:95]
	v_mfma_f32_16x16x32_bf16 v[96:99], v[214:217], v[226:229], v[96:99]
	v_mfma_f32_16x16x32_bf16 v[36:39], v[218:221], v[226:229], v[36:39]
	ds_read_b128 v[226:229], v31
	s_waitcnt lgkmcnt(3)
	v_mfma_f32_16x16x32_bf16 v[104:107], v[158:161], v[166:169], v[104:107]
	v_mfma_f32_16x16x32_bf16 v[108:111], v[162:165], v[166:169], v[108:111]
	v_mfma_f32_16x16x32_bf16 v[112:115], v[214:217], v[166:169], v[112:115]
	v_mfma_f32_16x16x32_bf16 v[52:55], v[218:221], v[166:169], v[52:55]
	s_waitcnt lgkmcnt(2)
	v_mfma_f32_16x16x32_bf16 v[116:119], v[158:161], v[178:181], v[116:119]
	v_mfma_f32_16x16x32_bf16 v[120:123], v[162:165], v[178:181], v[120:123]
	v_mfma_f32_16x16x32_bf16 v[124:127], v[214:217], v[178:181], v[124:127]
	v_mfma_f32_16x16x32_bf16 v[68:71], v[218:221], v[178:181], v[68:71]
	s_waitcnt lgkmcnt(1)
	v_mfma_f32_16x16x32_bf16 v[128:131], v[158:161], v[222:225], v[128:131]
	v_mfma_f32_16x16x32_bf16 v[132:135], v[162:165], v[222:225], v[132:135]
	v_mfma_f32_16x16x32_bf16 v[136:139], v[214:217], v[222:225], v[136:139]
	v_mfma_f32_16x16x32_bf16 v[84:87], v[218:221], v[222:225], v[84:87]
	s_waitcnt lgkmcnt(0)
	v_mfma_f32_16x16x32_bf16 v[100:103], v[158:161], v[226:229], v[100:103]
	v_mfma_f32_16x16x32_bf16 v[140:143], v[162:165], v[226:229], v[140:143]
	v_mfma_f32_16x16x32_bf16 v[150:153], v[214:217], v[226:229], v[150:153]
	v_mfma_f32_16x16x32_bf16 v[154:157], v[218:221], v[226:229], v[154:157]
	s_add_u32 s50, s14, 0x880
	s_addc_u32 s51, s15, 0
	s_add_u32 s52, s20, 0x880
	s_waitcnt vmcnt(0)
	s_barrier
	s_addc_u32 s53, s21, 0
	ds_read_b128 v[158:161], v7 offset:32768
	ds_read_b128 v[162:165], v6
	ds_read_b128 v[166:169], v7 offset:34816
	ds_read_b128 v[178:181], v6 offset:2048
	ds_read_b128 v[214:217], v7 offset:36864
	ds_read_b128 v[218:221], v7 offset:38912
	ds_read_b128 v[222:225], v6 offset:4096
	ds_read_b128 v[226:229], v6 offset:6144
	s_waitcnt lgkmcnt(6)
	v_mfma_f32_16x16x32_bf16 v[40:43], v[158:161], v[162:165], v[40:43]
	s_waitcnt lgkmcnt(5)
	v_mfma_f32_16x16x32_bf16 v[44:47], v[166:169], v[162:165], v[44:47]
	s_waitcnt lgkmcnt(4)
	v_mfma_f32_16x16x32_bf16 v[56:59], v[158:161], v[178:181], v[56:59]
	s_mov_b32 m0, s27
	v_mfma_f32_16x16x32_bf16 v[60:63], v[166:169], v[178:181], v[60:63]
	global_load_lds_dwordx4 v0, s[50:51]
	s_waitcnt lgkmcnt(3)
	v_mfma_f32_16x16x32_bf16 v[48:51], v[214:217], v[162:165], v[48:51]
	v_mfma_f32_16x16x32_bf16 v[64:67], v[214:217], v[178:181], v[64:67]
	s_waitcnt lgkmcnt(2)
	v_mfma_f32_16x16x32_bf16 v[174:177], v[218:221], v[162:165], v[174:177]
	ds_read_b128 v[162:165], v6 offset:8192
	v_mfma_f32_16x16x32_bf16 v[170:173], v[218:221], v[178:181], v[170:173]
	ds_read_b128 v[178:181], v6 offset:10240
	s_waitcnt lgkmcnt(3)
	s_mov_b32 m0, s26
	v_mfma_f32_16x16x32_bf16 v[72:75], v[158:161], v[222:225], v[72:75]
	global_load_lds_dwordx4 v0, s[52:53]
	v_mfma_f32_16x16x32_bf16 v[76:79], v[166:169], v[222:225], v[76:79]
	v_mfma_f32_16x16x32_bf16 v[80:83], v[214:217], v[222:225], v[80:83]
	v_mfma_f32_16x16x32_bf16 v[32:35], v[218:221], v[222:225], v[32:35]
	ds_read_b128 v[222:225], v6 offset:12288
	s_waitcnt lgkmcnt(3)
	v_mfma_f32_16x16x32_bf16 v[88:91], v[158:161], v[226:229], v[88:91]
	s_mov_b32 m0, s41
	v_mfma_f32_16x16x32_bf16 v[92:95], v[166:169], v[226:229], v[92:95]
	global_load_lds_dwordx4 v2, s[50:51]
	v_mfma_f32_16x16x32_bf16 v[96:99], v[214:217], v[226:229], v[96:99]
	v_mfma_f32_16x16x32_bf16 v[36:39], v[218:221], v[226:229], v[36:39]
	ds_read_b128 v[226:229], v6 offset:14336
	s_waitcnt lgkmcnt(3)
	v_mfma_f32_16x16x32_bf16 v[104:107], v[158:161], v[162:165], v[104:107]
	s_waitcnt lgkmcnt(2)
	v_mfma_f32_16x16x32_bf16 v[116:119], v[158:161], v[178:181], v[116:119]
	s_waitcnt lgkmcnt(1)
	s_mov_b32 m0, s42
	v_mfma_f32_16x16x32_bf16 v[128:131], v[158:161], v[222:225], v[128:131]
	global_load_lds_dwordx4 v2, s[52:53]
	s_waitcnt lgkmcnt(0)
	v_mfma_f32_16x16x32_bf16 v[100:103], v[158:161], v[226:229], v[100:103]
	ds_read_b128 v[158:161], v7 offset:33792
	v_mfma_f32_16x16x32_bf16 v[108:111], v[166:169], v[162:165], v[108:111]
	v_mfma_f32_16x16x32_bf16 v[120:123], v[166:169], v[178:181], v[120:123]
	v_mfma_f32_16x16x32_bf16 v[132:135], v[166:169], v[222:225], v[132:135]
	s_mov_b32 m0, s43
	v_mfma_f32_16x16x32_bf16 v[140:143], v[166:169], v[226:229], v[140:143]
	global_load_lds_dwordx4 v4, s[50:51]
	ds_read_b128 v[166:169], v6 offset:1024
	v_mfma_f32_16x16x32_bf16 v[112:115], v[214:217], v[162:165], v[112:115]
	v_mfma_f32_16x16x32_bf16 v[52:55], v[218:221], v[162:165], v[52:55]
	ds_read_b128 v[162:165], v7 offset:35840
	v_mfma_f32_16x16x32_bf16 v[124:127], v[214:217], v[178:181], v[124:127]
	v_mfma_f32_16x16x32_bf16 v[68:71], v[218:221], v[178:181], v[68:71]
	ds_read_b128 v[178:181], v6 offset:3072
	s_mov_b32 m0, s44
	v_mfma_f32_16x16x32_bf16 v[136:139], v[214:217], v[222:225], v[136:139]
	global_load_lds_dwordx4 v4, s[52:53]
	v_mfma_f32_16x16x32_bf16 v[84:87], v[218:221], v[222:225], v[84:87]
	ds_read_b128 v[222:225], v6 offset:5120
	v_mfma_f32_16x16x32_bf16 v[150:153], v[214:217], v[226:229], v[150:153]
	ds_read_b128 v[214:217], v7 offset:37888
	v_mfma_f32_16x16x32_bf16 v[154:157], v[218:221], v[226:229], v[154:157]
	ds_read_b128 v[218:221], v7 offset:39936
	ds_read_b128 v[226:229], v6 offset:7168
	s_waitcnt lgkmcnt(6)
	v_mfma_f32_16x16x32_bf16 v[40:43], v[158:161], v[166:169], v[40:43]
	s_waitcnt lgkmcnt(5)
	s_mov_b32 m0, s45
	v_mfma_f32_16x16x32_bf16 v[44:47], v[162:165], v[166:169], v[44:47]
	global_load_lds_dwordx4 v146, s[50:51]
	s_waitcnt lgkmcnt(4)
	v_mfma_f32_16x16x32_bf16 v[56:59], v[158:161], v[178:181], v[56:59]
	v_mfma_f32_16x16x32_bf16 v[60:63], v[162:165], v[178:181], v[60:63]
	s_waitcnt lgkmcnt(3)
	v_mfma_f32_16x16x32_bf16 v[72:75], v[158:161], v[222:225], v[72:75]
	v_mfma_f32_16x16x32_bf16 v[76:79], v[162:165], v[222:225], v[76:79]
	s_waitcnt lgkmcnt(2)
	s_mov_b32 m0, s46
	v_mfma_f32_16x16x32_bf16 v[48:51], v[214:217], v[166:169], v[48:51]
	global_load_lds_dwordx4 v146, s[52:53]
	s_waitcnt lgkmcnt(1)
	v_mfma_f32_16x16x32_bf16 v[174:177], v[218:221], v[166:169], v[174:177]
	ds_read_b128 v[166:169], v6 offset:9216
	v_mfma_f32_16x16x32_bf16 v[64:67], v[214:217], v[178:181], v[64:67]
	v_mfma_f32_16x16x32_bf16 v[170:173], v[218:221], v[178:181], v[170:173]
	ds_read_b128 v[178:181], v6 offset:11264
	v_mfma_f32_16x16x32_bf16 v[80:83], v[214:217], v[222:225], v[80:83]
	v_mfma_f32_16x16x32_bf16 v[32:35], v[218:221], v[222:225], v[32:35]
	ds_read_b128 v[222:225], v6 offset:13312
	s_waitcnt lgkmcnt(3)
	v_mfma_f32_16x16x32_bf16 v[88:91], v[158:161], v[226:229], v[88:91]
	v_mfma_f32_16x16x32_bf16 v[92:95], v[162:165], v[226:229], v[92:95]
	v_mfma_f32_16x16x32_bf16 v[96:99], v[214:217], v[226:229], v[96:99]
	v_mfma_f32_16x16x32_bf16 v[36:39], v[218:221], v[226:229], v[36:39]
	ds_read_b128 v[226:229], v6 offset:15360
	s_waitcnt lgkmcnt(3)
	v_mfma_f32_16x16x32_bf16 v[104:107], v[158:161], v[166:169], v[104:107]
	v_mfma_f32_16x16x32_bf16 v[108:111], v[162:165], v[166:169], v[108:111]
	v_mfma_f32_16x16x32_bf16 v[112:115], v[214:217], v[166:169], v[112:115]
	v_mfma_f32_16x16x32_bf16 v[52:55], v[218:221], v[166:169], v[52:55]
	s_waitcnt lgkmcnt(2)
	v_mfma_f32_16x16x32_bf16 v[116:119], v[158:161], v[178:181], v[116:119]
	v_mfma_f32_16x16x32_bf16 v[120:123], v[162:165], v[178:181], v[120:123]
	v_mfma_f32_16x16x32_bf16 v[124:127], v[214:217], v[178:181], v[124:127]
	v_mfma_f32_16x16x32_bf16 v[68:71], v[218:221], v[178:181], v[68:71]
	s_waitcnt lgkmcnt(1)
	v_mfma_f32_16x16x32_bf16 v[128:131], v[158:161], v[222:225], v[128:131]
	v_mfma_f32_16x16x32_bf16 v[132:135], v[162:165], v[222:225], v[132:135]
	v_mfma_f32_16x16x32_bf16 v[136:139], v[214:217], v[222:225], v[136:139]
	v_mfma_f32_16x16x32_bf16 v[84:87], v[218:221], v[222:225], v[84:87]
	s_waitcnt lgkmcnt(0)
	v_mfma_f32_16x16x32_bf16 v[100:103], v[158:161], v[226:229], v[100:103]
	v_mfma_f32_16x16x32_bf16 v[140:143], v[162:165], v[226:229], v[140:143]
	v_mfma_f32_16x16x32_bf16 v[150:153], v[214:217], v[226:229], v[150:153]
	v_mfma_f32_16x16x32_bf16 v[154:157], v[218:221], v[226:229], v[154:157]
	s_add_u32 s50, s14, 0x900
	s_addc_u32 s51, s15, 0
	s_add_u32 s52, s20, 0x900
	s_waitcnt vmcnt(0)
	s_barrier
	s_addc_u32 s53, s21, 0
	ds_read_b128 v[158:161], v8
	ds_read_b128 v[162:165], v12
	ds_read_b128 v[166:169], v9
	ds_read_b128 v[178:181], v13
	ds_read_b128 v[214:217], v11
	ds_read_b128 v[218:221], v10
	ds_read_b128 v[222:225], v14
	ds_read_b128 v[226:229], v15
	s_waitcnt lgkmcnt(6)
	v_mfma_f32_16x16x32_bf16 v[40:43], v[158:161], v[162:165], v[40:43]
	s_waitcnt lgkmcnt(5)
	v_mfma_f32_16x16x32_bf16 v[44:47], v[166:169], v[162:165], v[44:47]
	s_waitcnt lgkmcnt(4)
	v_mfma_f32_16x16x32_bf16 v[56:59], v[158:161], v[178:181], v[56:59]
	s_mov_b32 m0, s1
	v_mfma_f32_16x16x32_bf16 v[60:63], v[166:169], v[178:181], v[60:63]
	global_load_lds_dwordx4 v0, s[50:51]
	s_waitcnt lgkmcnt(3)
	v_mfma_f32_16x16x32_bf16 v[48:51], v[214:217], v[162:165], v[48:51]
	v_mfma_f32_16x16x32_bf16 v[64:67], v[214:217], v[178:181], v[64:67]
	s_waitcnt lgkmcnt(2)
	v_mfma_f32_16x16x32_bf16 v[174:177], v[218:221], v[162:165], v[174:177]
	ds_read_b128 v[162:165], v16
	v_mfma_f32_16x16x32_bf16 v[170:173], v[218:221], v[178:181], v[170:173]
	ds_read_b128 v[178:181], v17
	s_waitcnt lgkmcnt(3)
	s_mov_b32 m0, s34
	v_mfma_f32_16x16x32_bf16 v[72:75], v[158:161], v[222:225], v[72:75]
	global_load_lds_dwordx4 v0, s[52:53]
	v_mfma_f32_16x16x32_bf16 v[76:79], v[166:169], v[222:225], v[76:79]
	v_mfma_f32_16x16x32_bf16 v[80:83], v[214:217], v[222:225], v[80:83]
	v_mfma_f32_16x16x32_bf16 v[32:35], v[218:221], v[222:225], v[32:35]
	ds_read_b128 v[222:225], v18
	s_waitcnt lgkmcnt(3)
	v_mfma_f32_16x16x32_bf16 v[88:91], v[158:161], v[226:229], v[88:91]
	s_mov_b32 m0, s35
	v_mfma_f32_16x16x32_bf16 v[92:95], v[166:169], v[226:229], v[92:95]
	global_load_lds_dwordx4 v2, s[50:51]
	v_mfma_f32_16x16x32_bf16 v[96:99], v[214:217], v[226:229], v[96:99]
	v_mfma_f32_16x16x32_bf16 v[36:39], v[218:221], v[226:229], v[36:39]
	ds_read_b128 v[226:229], v19
	s_waitcnt lgkmcnt(3)
	v_mfma_f32_16x16x32_bf16 v[104:107], v[158:161], v[162:165], v[104:107]
	s_waitcnt lgkmcnt(2)
	v_mfma_f32_16x16x32_bf16 v[116:119], v[158:161], v[178:181], v[116:119]
	s_waitcnt lgkmcnt(1)
	s_mov_b32 m0, s36
	v_mfma_f32_16x16x32_bf16 v[128:131], v[158:161], v[222:225], v[128:131]
	global_load_lds_dwordx4 v2, s[52:53]
	s_waitcnt lgkmcnt(0)
	v_mfma_f32_16x16x32_bf16 v[100:103], v[158:161], v[226:229], v[100:103]
	ds_read_b128 v[158:161], v20
	v_mfma_f32_16x16x32_bf16 v[108:111], v[166:169], v[162:165], v[108:111]
	v_mfma_f32_16x16x32_bf16 v[120:123], v[166:169], v[178:181], v[120:123]
	v_mfma_f32_16x16x32_bf16 v[132:135], v[166:169], v[222:225], v[132:135]
	s_mov_b32 m0, s37
	v_mfma_f32_16x16x32_bf16 v[140:143], v[166:169], v[226:229], v[140:143]
	global_load_lds_dwordx4 v4, s[50:51]
	ds_read_b128 v[166:169], v24
	v_mfma_f32_16x16x32_bf16 v[112:115], v[214:217], v[162:165], v[112:115]
	v_mfma_f32_16x16x32_bf16 v[52:55], v[218:221], v[162:165], v[52:55]
	ds_read_b128 v[162:165], v21
	v_mfma_f32_16x16x32_bf16 v[124:127], v[214:217], v[178:181], v[124:127]
	v_mfma_f32_16x16x32_bf16 v[68:71], v[218:221], v[178:181], v[68:71]
	ds_read_b128 v[178:181], v25
	s_mov_b32 m0, s38
	v_mfma_f32_16x16x32_bf16 v[136:139], v[214:217], v[222:225], v[136:139]
	global_load_lds_dwordx4 v4, s[52:53]
	v_mfma_f32_16x16x32_bf16 v[84:87], v[218:221], v[222:225], v[84:87]
	ds_read_b128 v[222:225], v26
	v_mfma_f32_16x16x32_bf16 v[150:153], v[214:217], v[226:229], v[150:153]
	ds_read_b128 v[214:217], v23
	v_mfma_f32_16x16x32_bf16 v[154:157], v[218:221], v[226:229], v[154:157]
	ds_read_b128 v[218:221], v22
	ds_read_b128 v[226:229], v27
	s_waitcnt lgkmcnt(6)
	v_mfma_f32_16x16x32_bf16 v[40:43], v[158:161], v[166:169], v[40:43]
	s_waitcnt lgkmcnt(5)
	s_mov_b32 m0, s39
	v_mfma_f32_16x16x32_bf16 v[44:47], v[162:165], v[166:169], v[44:47]
	global_load_lds_dwordx4 v146, s[50:51]
	s_waitcnt lgkmcnt(4)
	v_mfma_f32_16x16x32_bf16 v[56:59], v[158:161], v[178:181], v[56:59]
	v_mfma_f32_16x16x32_bf16 v[60:63], v[162:165], v[178:181], v[60:63]
	s_waitcnt lgkmcnt(3)
	v_mfma_f32_16x16x32_bf16 v[72:75], v[158:161], v[222:225], v[72:75]
	v_mfma_f32_16x16x32_bf16 v[76:79], v[162:165], v[222:225], v[76:79]
	s_waitcnt lgkmcnt(2)
	s_mov_b32 m0, s40
	v_mfma_f32_16x16x32_bf16 v[48:51], v[214:217], v[166:169], v[48:51]
	global_load_lds_dwordx4 v146, s[52:53]
	s_waitcnt lgkmcnt(1)
	v_mfma_f32_16x16x32_bf16 v[174:177], v[218:221], v[166:169], v[174:177]
	ds_read_b128 v[166:169], v28
	v_mfma_f32_16x16x32_bf16 v[64:67], v[214:217], v[178:181], v[64:67]
	v_mfma_f32_16x16x32_bf16 v[170:173], v[218:221], v[178:181], v[170:173]
	ds_read_b128 v[178:181], v29
	v_mfma_f32_16x16x32_bf16 v[80:83], v[214:217], v[222:225], v[80:83]
	v_mfma_f32_16x16x32_bf16 v[32:35], v[218:221], v[222:225], v[32:35]
	ds_read_b128 v[222:225], v30
	s_waitcnt lgkmcnt(3)
	v_mfma_f32_16x16x32_bf16 v[88:91], v[158:161], v[226:229], v[88:91]
	v_mfma_f32_16x16x32_bf16 v[92:95], v[162:165], v[226:229], v[92:95]
	v_mfma_f32_16x16x32_bf16 v[96:99], v[214:217], v[226:229], v[96:99]
	v_mfma_f32_16x16x32_bf16 v[36:39], v[218:221], v[226:229], v[36:39]
	ds_read_b128 v[226:229], v31
	s_waitcnt lgkmcnt(3)
	v_mfma_f32_16x16x32_bf16 v[104:107], v[158:161], v[166:169], v[104:107]
	v_mfma_f32_16x16x32_bf16 v[108:111], v[162:165], v[166:169], v[108:111]
	v_mfma_f32_16x16x32_bf16 v[112:115], v[214:217], v[166:169], v[112:115]
	v_mfma_f32_16x16x32_bf16 v[52:55], v[218:221], v[166:169], v[52:55]
	s_waitcnt lgkmcnt(2)
	v_mfma_f32_16x16x32_bf16 v[116:119], v[158:161], v[178:181], v[116:119]
	v_mfma_f32_16x16x32_bf16 v[120:123], v[162:165], v[178:181], v[120:123]
	v_mfma_f32_16x16x32_bf16 v[124:127], v[214:217], v[178:181], v[124:127]
	v_mfma_f32_16x16x32_bf16 v[68:71], v[218:221], v[178:181], v[68:71]
	s_waitcnt lgkmcnt(1)
	v_mfma_f32_16x16x32_bf16 v[128:131], v[158:161], v[222:225], v[128:131]
	v_mfma_f32_16x16x32_bf16 v[132:135], v[162:165], v[222:225], v[132:135]
	v_mfma_f32_16x16x32_bf16 v[136:139], v[214:217], v[222:225], v[136:139]
	v_mfma_f32_16x16x32_bf16 v[84:87], v[218:221], v[222:225], v[84:87]
	s_waitcnt lgkmcnt(0)
	v_mfma_f32_16x16x32_bf16 v[100:103], v[158:161], v[226:229], v[100:103]
	v_mfma_f32_16x16x32_bf16 v[140:143], v[162:165], v[226:229], v[140:143]
	v_mfma_f32_16x16x32_bf16 v[150:153], v[214:217], v[226:229], v[150:153]
	v_mfma_f32_16x16x32_bf16 v[154:157], v[218:221], v[226:229], v[154:157]
	s_add_u32 s50, s14, 0x980
	s_addc_u32 s51, s15, 0
	s_add_u32 s52, s20, 0x980
	s_waitcnt vmcnt(0)
	s_barrier
	s_addc_u32 s53, s21, 0
	ds_read_b128 v[158:161], v7 offset:32768
	ds_read_b128 v[162:165], v6
	ds_read_b128 v[166:169], v7 offset:34816
	ds_read_b128 v[178:181], v6 offset:2048
	ds_read_b128 v[214:217], v7 offset:36864
	ds_read_b128 v[218:221], v7 offset:38912
	ds_read_b128 v[222:225], v6 offset:4096
	ds_read_b128 v[226:229], v6 offset:6144
	s_waitcnt lgkmcnt(6)
	v_mfma_f32_16x16x32_bf16 v[40:43], v[158:161], v[162:165], v[40:43]
	s_waitcnt lgkmcnt(5)
	v_mfma_f32_16x16x32_bf16 v[44:47], v[166:169], v[162:165], v[44:47]
	s_waitcnt lgkmcnt(4)
	v_mfma_f32_16x16x32_bf16 v[56:59], v[158:161], v[178:181], v[56:59]
	s_mov_b32 m0, s27
	v_mfma_f32_16x16x32_bf16 v[60:63], v[166:169], v[178:181], v[60:63]
	global_load_lds_dwordx4 v0, s[50:51]
	s_waitcnt lgkmcnt(3)
	v_mfma_f32_16x16x32_bf16 v[48:51], v[214:217], v[162:165], v[48:51]
	v_mfma_f32_16x16x32_bf16 v[64:67], v[214:217], v[178:181], v[64:67]
	s_waitcnt lgkmcnt(2)
	v_mfma_f32_16x16x32_bf16 v[174:177], v[218:221], v[162:165], v[174:177]
	ds_read_b128 v[162:165], v6 offset:8192
	v_mfma_f32_16x16x32_bf16 v[170:173], v[218:221], v[178:181], v[170:173]
	ds_read_b128 v[178:181], v6 offset:10240
	s_waitcnt lgkmcnt(3)
	s_mov_b32 m0, s26
	v_mfma_f32_16x16x32_bf16 v[72:75], v[158:161], v[222:225], v[72:75]
	global_load_lds_dwordx4 v0, s[52:53]
	v_mfma_f32_16x16x32_bf16 v[76:79], v[166:169], v[222:225], v[76:79]
	v_mfma_f32_16x16x32_bf16 v[80:83], v[214:217], v[222:225], v[80:83]
	v_mfma_f32_16x16x32_bf16 v[32:35], v[218:221], v[222:225], v[32:35]
	ds_read_b128 v[222:225], v6 offset:12288
	s_waitcnt lgkmcnt(3)
	v_mfma_f32_16x16x32_bf16 v[88:91], v[158:161], v[226:229], v[88:91]
	s_mov_b32 m0, s41
	v_mfma_f32_16x16x32_bf16 v[92:95], v[166:169], v[226:229], v[92:95]
	global_load_lds_dwordx4 v2, s[50:51]
	v_mfma_f32_16x16x32_bf16 v[96:99], v[214:217], v[226:229], v[96:99]
	v_mfma_f32_16x16x32_bf16 v[36:39], v[218:221], v[226:229], v[36:39]
	ds_read_b128 v[226:229], v6 offset:14336
	s_waitcnt lgkmcnt(3)
	v_mfma_f32_16x16x32_bf16 v[104:107], v[158:161], v[162:165], v[104:107]
	s_waitcnt lgkmcnt(2)
	v_mfma_f32_16x16x32_bf16 v[116:119], v[158:161], v[178:181], v[116:119]
	s_waitcnt lgkmcnt(1)
	s_mov_b32 m0, s42
	v_mfma_f32_16x16x32_bf16 v[128:131], v[158:161], v[222:225], v[128:131]
	global_load_lds_dwordx4 v2, s[52:53]
	s_waitcnt lgkmcnt(0)
	v_mfma_f32_16x16x32_bf16 v[100:103], v[158:161], v[226:229], v[100:103]
	ds_read_b128 v[158:161], v7 offset:33792
	v_mfma_f32_16x16x32_bf16 v[108:111], v[166:169], v[162:165], v[108:111]
	v_mfma_f32_16x16x32_bf16 v[120:123], v[166:169], v[178:181], v[120:123]
	v_mfma_f32_16x16x32_bf16 v[132:135], v[166:169], v[222:225], v[132:135]
	s_mov_b32 m0, s43
	v_mfma_f32_16x16x32_bf16 v[140:143], v[166:169], v[226:229], v[140:143]
	global_load_lds_dwordx4 v4, s[50:51]
	ds_read_b128 v[166:169], v6 offset:1024
	v_mfma_f32_16x16x32_bf16 v[112:115], v[214:217], v[162:165], v[112:115]
	v_mfma_f32_16x16x32_bf16 v[52:55], v[218:221], v[162:165], v[52:55]
	ds_read_b128 v[162:165], v7 offset:35840
	v_mfma_f32_16x16x32_bf16 v[124:127], v[214:217], v[178:181], v[124:127]
	v_mfma_f32_16x16x32_bf16 v[68:71], v[218:221], v[178:181], v[68:71]
	ds_read_b128 v[178:181], v6 offset:3072
	s_mov_b32 m0, s44
	v_mfma_f32_16x16x32_bf16 v[136:139], v[214:217], v[222:225], v[136:139]
	global_load_lds_dwordx4 v4, s[52:53]
	v_mfma_f32_16x16x32_bf16 v[84:87], v[218:221], v[222:225], v[84:87]
	ds_read_b128 v[222:225], v6 offset:5120
	v_mfma_f32_16x16x32_bf16 v[150:153], v[214:217], v[226:229], v[150:153]
	ds_read_b128 v[214:217], v7 offset:37888
	v_mfma_f32_16x16x32_bf16 v[154:157], v[218:221], v[226:229], v[154:157]
	ds_read_b128 v[218:221], v7 offset:39936
	ds_read_b128 v[226:229], v6 offset:7168
	s_waitcnt lgkmcnt(6)
	v_mfma_f32_16x16x32_bf16 v[40:43], v[158:161], v[166:169], v[40:43]
	s_waitcnt lgkmcnt(5)
	s_mov_b32 m0, s45
	v_mfma_f32_16x16x32_bf16 v[44:47], v[162:165], v[166:169], v[44:47]
	global_load_lds_dwordx4 v146, s[50:51]
	s_waitcnt lgkmcnt(4)
	v_mfma_f32_16x16x32_bf16 v[56:59], v[158:161], v[178:181], v[56:59]
	v_mfma_f32_16x16x32_bf16 v[60:63], v[162:165], v[178:181], v[60:63]
	s_waitcnt lgkmcnt(3)
	v_mfma_f32_16x16x32_bf16 v[72:75], v[158:161], v[222:225], v[72:75]
	v_mfma_f32_16x16x32_bf16 v[76:79], v[162:165], v[222:225], v[76:79]
	s_waitcnt lgkmcnt(2)
	s_mov_b32 m0, s46
	v_mfma_f32_16x16x32_bf16 v[48:51], v[214:217], v[166:169], v[48:51]
	global_load_lds_dwordx4 v146, s[52:53]
	s_waitcnt lgkmcnt(1)
	v_mfma_f32_16x16x32_bf16 v[174:177], v[218:221], v[166:169], v[174:177]
	ds_read_b128 v[166:169], v6 offset:9216
	v_mfma_f32_16x16x32_bf16 v[64:67], v[214:217], v[178:181], v[64:67]
	v_mfma_f32_16x16x32_bf16 v[170:173], v[218:221], v[178:181], v[170:173]
	ds_read_b128 v[178:181], v6 offset:11264
	v_mfma_f32_16x16x32_bf16 v[80:83], v[214:217], v[222:225], v[80:83]
	v_mfma_f32_16x16x32_bf16 v[32:35], v[218:221], v[222:225], v[32:35]
	ds_read_b128 v[222:225], v6 offset:13312
	s_waitcnt lgkmcnt(3)
	v_mfma_f32_16x16x32_bf16 v[88:91], v[158:161], v[226:229], v[88:91]
	v_mfma_f32_16x16x32_bf16 v[92:95], v[162:165], v[226:229], v[92:95]
	v_mfma_f32_16x16x32_bf16 v[96:99], v[214:217], v[226:229], v[96:99]
	v_mfma_f32_16x16x32_bf16 v[36:39], v[218:221], v[226:229], v[36:39]
	ds_read_b128 v[226:229], v6 offset:15360
	s_waitcnt lgkmcnt(3)
	v_mfma_f32_16x16x32_bf16 v[104:107], v[158:161], v[166:169], v[104:107]
	v_mfma_f32_16x16x32_bf16 v[108:111], v[162:165], v[166:169], v[108:111]
	v_mfma_f32_16x16x32_bf16 v[112:115], v[214:217], v[166:169], v[112:115]
	v_mfma_f32_16x16x32_bf16 v[52:55], v[218:221], v[166:169], v[52:55]
	s_waitcnt lgkmcnt(2)
	v_mfma_f32_16x16x32_bf16 v[116:119], v[158:161], v[178:181], v[116:119]
	v_mfma_f32_16x16x32_bf16 v[120:123], v[162:165], v[178:181], v[120:123]
	v_mfma_f32_16x16x32_bf16 v[124:127], v[214:217], v[178:181], v[124:127]
	v_mfma_f32_16x16x32_bf16 v[68:71], v[218:221], v[178:181], v[68:71]
	s_waitcnt lgkmcnt(1)
	v_mfma_f32_16x16x32_bf16 v[128:131], v[158:161], v[222:225], v[128:131]
	v_mfma_f32_16x16x32_bf16 v[132:135], v[162:165], v[222:225], v[132:135]
	v_mfma_f32_16x16x32_bf16 v[136:139], v[214:217], v[222:225], v[136:139]
	v_mfma_f32_16x16x32_bf16 v[84:87], v[218:221], v[222:225], v[84:87]
	s_waitcnt lgkmcnt(0)
	v_mfma_f32_16x16x32_bf16 v[100:103], v[158:161], v[226:229], v[100:103]
	v_mfma_f32_16x16x32_bf16 v[140:143], v[162:165], v[226:229], v[140:143]
	v_mfma_f32_16x16x32_bf16 v[150:153], v[214:217], v[226:229], v[150:153]
	v_mfma_f32_16x16x32_bf16 v[154:157], v[218:221], v[226:229], v[154:157]
	s_add_u32 s50, s14, 0xa00
	s_addc_u32 s51, s15, 0
	s_add_u32 s52, s20, 0xa00
	s_waitcnt vmcnt(0)
	s_barrier
	s_addc_u32 s53, s21, 0
	ds_read_b128 v[158:161], v8
	ds_read_b128 v[162:165], v12
	ds_read_b128 v[166:169], v9
	ds_read_b128 v[178:181], v13
	ds_read_b128 v[214:217], v11
	ds_read_b128 v[218:221], v10
	ds_read_b128 v[222:225], v14
	ds_read_b128 v[226:229], v15
	s_waitcnt lgkmcnt(6)
	v_mfma_f32_16x16x32_bf16 v[40:43], v[158:161], v[162:165], v[40:43]
	s_waitcnt lgkmcnt(5)
	v_mfma_f32_16x16x32_bf16 v[44:47], v[166:169], v[162:165], v[44:47]
	s_waitcnt lgkmcnt(4)
	v_mfma_f32_16x16x32_bf16 v[56:59], v[158:161], v[178:181], v[56:59]
	s_mov_b32 m0, s1
	v_mfma_f32_16x16x32_bf16 v[60:63], v[166:169], v[178:181], v[60:63]
	global_load_lds_dwordx4 v0, s[50:51]
	s_waitcnt lgkmcnt(3)
	v_mfma_f32_16x16x32_bf16 v[48:51], v[214:217], v[162:165], v[48:51]
	v_mfma_f32_16x16x32_bf16 v[64:67], v[214:217], v[178:181], v[64:67]
	s_waitcnt lgkmcnt(2)
	v_mfma_f32_16x16x32_bf16 v[174:177], v[218:221], v[162:165], v[174:177]
	ds_read_b128 v[162:165], v16
	v_mfma_f32_16x16x32_bf16 v[170:173], v[218:221], v[178:181], v[170:173]
	ds_read_b128 v[178:181], v17
	s_waitcnt lgkmcnt(3)
	s_mov_b32 m0, s34
	v_mfma_f32_16x16x32_bf16 v[72:75], v[158:161], v[222:225], v[72:75]
	global_load_lds_dwordx4 v0, s[52:53]
	v_mfma_f32_16x16x32_bf16 v[76:79], v[166:169], v[222:225], v[76:79]
	v_mfma_f32_16x16x32_bf16 v[80:83], v[214:217], v[222:225], v[80:83]
	v_mfma_f32_16x16x32_bf16 v[32:35], v[218:221], v[222:225], v[32:35]
	ds_read_b128 v[222:225], v18
	s_waitcnt lgkmcnt(3)
	v_mfma_f32_16x16x32_bf16 v[88:91], v[158:161], v[226:229], v[88:91]
	s_mov_b32 m0, s35
	v_mfma_f32_16x16x32_bf16 v[92:95], v[166:169], v[226:229], v[92:95]
	global_load_lds_dwordx4 v2, s[50:51]
	v_mfma_f32_16x16x32_bf16 v[96:99], v[214:217], v[226:229], v[96:99]
	v_mfma_f32_16x16x32_bf16 v[36:39], v[218:221], v[226:229], v[36:39]
	ds_read_b128 v[226:229], v19
	s_waitcnt lgkmcnt(3)
	v_mfma_f32_16x16x32_bf16 v[104:107], v[158:161], v[162:165], v[104:107]
	s_waitcnt lgkmcnt(2)
	v_mfma_f32_16x16x32_bf16 v[116:119], v[158:161], v[178:181], v[116:119]
	s_waitcnt lgkmcnt(1)
	s_mov_b32 m0, s36
	v_mfma_f32_16x16x32_bf16 v[128:131], v[158:161], v[222:225], v[128:131]
	global_load_lds_dwordx4 v2, s[52:53]
	s_waitcnt lgkmcnt(0)
	v_mfma_f32_16x16x32_bf16 v[100:103], v[158:161], v[226:229], v[100:103]
	ds_read_b128 v[158:161], v20
	v_mfma_f32_16x16x32_bf16 v[108:111], v[166:169], v[162:165], v[108:111]
	v_mfma_f32_16x16x32_bf16 v[120:123], v[166:169], v[178:181], v[120:123]
	v_mfma_f32_16x16x32_bf16 v[132:135], v[166:169], v[222:225], v[132:135]
	s_mov_b32 m0, s37
	v_mfma_f32_16x16x32_bf16 v[140:143], v[166:169], v[226:229], v[140:143]
	global_load_lds_dwordx4 v4, s[50:51]
	ds_read_b128 v[166:169], v24
	v_mfma_f32_16x16x32_bf16 v[112:115], v[214:217], v[162:165], v[112:115]
	v_mfma_f32_16x16x32_bf16 v[52:55], v[218:221], v[162:165], v[52:55]
	ds_read_b128 v[162:165], v21
	v_mfma_f32_16x16x32_bf16 v[124:127], v[214:217], v[178:181], v[124:127]
	v_mfma_f32_16x16x32_bf16 v[68:71], v[218:221], v[178:181], v[68:71]
	ds_read_b128 v[178:181], v25
	s_mov_b32 m0, s38
	v_mfma_f32_16x16x32_bf16 v[136:139], v[214:217], v[222:225], v[136:139]
	global_load_lds_dwordx4 v4, s[52:53]
	v_mfma_f32_16x16x32_bf16 v[84:87], v[218:221], v[222:225], v[84:87]
	ds_read_b128 v[222:225], v26
	v_mfma_f32_16x16x32_bf16 v[150:153], v[214:217], v[226:229], v[150:153]
	ds_read_b128 v[214:217], v23
	v_mfma_f32_16x16x32_bf16 v[154:157], v[218:221], v[226:229], v[154:157]
	ds_read_b128 v[218:221], v22
	ds_read_b128 v[226:229], v27
	s_waitcnt lgkmcnt(6)
	v_mfma_f32_16x16x32_bf16 v[40:43], v[158:161], v[166:169], v[40:43]
	s_waitcnt lgkmcnt(5)
	s_mov_b32 m0, s39
	v_mfma_f32_16x16x32_bf16 v[44:47], v[162:165], v[166:169], v[44:47]
	global_load_lds_dwordx4 v146, s[50:51]
	s_waitcnt lgkmcnt(4)
	v_mfma_f32_16x16x32_bf16 v[56:59], v[158:161], v[178:181], v[56:59]
	v_mfma_f32_16x16x32_bf16 v[60:63], v[162:165], v[178:181], v[60:63]
	s_waitcnt lgkmcnt(3)
	v_mfma_f32_16x16x32_bf16 v[72:75], v[158:161], v[222:225], v[72:75]
	v_mfma_f32_16x16x32_bf16 v[76:79], v[162:165], v[222:225], v[76:79]
	s_waitcnt lgkmcnt(2)
	s_mov_b32 m0, s40
	v_mfma_f32_16x16x32_bf16 v[48:51], v[214:217], v[166:169], v[48:51]
	global_load_lds_dwordx4 v146, s[52:53]
	s_waitcnt lgkmcnt(1)
	v_mfma_f32_16x16x32_bf16 v[174:177], v[218:221], v[166:169], v[174:177]
	ds_read_b128 v[166:169], v28
	v_mfma_f32_16x16x32_bf16 v[64:67], v[214:217], v[178:181], v[64:67]
	v_mfma_f32_16x16x32_bf16 v[170:173], v[218:221], v[178:181], v[170:173]
	ds_read_b128 v[178:181], v29
	v_mfma_f32_16x16x32_bf16 v[80:83], v[214:217], v[222:225], v[80:83]
	v_mfma_f32_16x16x32_bf16 v[32:35], v[218:221], v[222:225], v[32:35]
	ds_read_b128 v[222:225], v30
	s_waitcnt lgkmcnt(3)
	v_mfma_f32_16x16x32_bf16 v[88:91], v[158:161], v[226:229], v[88:91]
	v_mfma_f32_16x16x32_bf16 v[92:95], v[162:165], v[226:229], v[92:95]
	v_mfma_f32_16x16x32_bf16 v[96:99], v[214:217], v[226:229], v[96:99]
	v_mfma_f32_16x16x32_bf16 v[36:39], v[218:221], v[226:229], v[36:39]
	ds_read_b128 v[226:229], v31
	s_waitcnt lgkmcnt(3)
	v_mfma_f32_16x16x32_bf16 v[104:107], v[158:161], v[166:169], v[104:107]
	v_mfma_f32_16x16x32_bf16 v[108:111], v[162:165], v[166:169], v[108:111]
	v_mfma_f32_16x16x32_bf16 v[112:115], v[214:217], v[166:169], v[112:115]
	v_mfma_f32_16x16x32_bf16 v[52:55], v[218:221], v[166:169], v[52:55]
	s_waitcnt lgkmcnt(2)
	v_mfma_f32_16x16x32_bf16 v[116:119], v[158:161], v[178:181], v[116:119]
	v_mfma_f32_16x16x32_bf16 v[120:123], v[162:165], v[178:181], v[120:123]
	v_mfma_f32_16x16x32_bf16 v[124:127], v[214:217], v[178:181], v[124:127]
	v_mfma_f32_16x16x32_bf16 v[68:71], v[218:221], v[178:181], v[68:71]
	s_waitcnt lgkmcnt(1)
	v_mfma_f32_16x16x32_bf16 v[128:131], v[158:161], v[222:225], v[128:131]
	v_mfma_f32_16x16x32_bf16 v[132:135], v[162:165], v[222:225], v[132:135]
	v_mfma_f32_16x16x32_bf16 v[136:139], v[214:217], v[222:225], v[136:139]
	v_mfma_f32_16x16x32_bf16 v[84:87], v[218:221], v[222:225], v[84:87]
	s_waitcnt lgkmcnt(0)
	v_mfma_f32_16x16x32_bf16 v[100:103], v[158:161], v[226:229], v[100:103]
	v_mfma_f32_16x16x32_bf16 v[140:143], v[162:165], v[226:229], v[140:143]
	v_mfma_f32_16x16x32_bf16 v[150:153], v[214:217], v[226:229], v[150:153]
	v_mfma_f32_16x16x32_bf16 v[154:157], v[218:221], v[226:229], v[154:157]
	s_add_u32 s50, s14, 0xa80
	s_addc_u32 s51, s15, 0
	s_add_u32 s52, s20, 0xa80
	s_waitcnt vmcnt(0)
	s_barrier
	s_addc_u32 s53, s21, 0
	ds_read_b128 v[158:161], v7 offset:32768
	ds_read_b128 v[162:165], v6
	ds_read_b128 v[166:169], v7 offset:34816
	ds_read_b128 v[178:181], v6 offset:2048
	ds_read_b128 v[214:217], v7 offset:36864
	ds_read_b128 v[218:221], v7 offset:38912
	ds_read_b128 v[222:225], v6 offset:4096
	ds_read_b128 v[226:229], v6 offset:6144
	s_waitcnt lgkmcnt(6)
	v_mfma_f32_16x16x32_bf16 v[40:43], v[158:161], v[162:165], v[40:43]
	s_waitcnt lgkmcnt(5)
	v_mfma_f32_16x16x32_bf16 v[44:47], v[166:169], v[162:165], v[44:47]
	s_waitcnt lgkmcnt(4)
	v_mfma_f32_16x16x32_bf16 v[56:59], v[158:161], v[178:181], v[56:59]
	s_mov_b32 m0, s27
	v_mfma_f32_16x16x32_bf16 v[60:63], v[166:169], v[178:181], v[60:63]
	global_load_lds_dwordx4 v0, s[50:51]
	s_waitcnt lgkmcnt(3)
	v_mfma_f32_16x16x32_bf16 v[48:51], v[214:217], v[162:165], v[48:51]
	v_mfma_f32_16x16x32_bf16 v[64:67], v[214:217], v[178:181], v[64:67]
	s_waitcnt lgkmcnt(2)
	v_mfma_f32_16x16x32_bf16 v[174:177], v[218:221], v[162:165], v[174:177]
	ds_read_b128 v[162:165], v6 offset:8192
	v_mfma_f32_16x16x32_bf16 v[170:173], v[218:221], v[178:181], v[170:173]
	ds_read_b128 v[178:181], v6 offset:10240
	s_waitcnt lgkmcnt(3)
	s_mov_b32 m0, s26
	v_mfma_f32_16x16x32_bf16 v[72:75], v[158:161], v[222:225], v[72:75]
	global_load_lds_dwordx4 v0, s[52:53]
	v_mfma_f32_16x16x32_bf16 v[76:79], v[166:169], v[222:225], v[76:79]
	v_mfma_f32_16x16x32_bf16 v[80:83], v[214:217], v[222:225], v[80:83]
	v_mfma_f32_16x16x32_bf16 v[32:35], v[218:221], v[222:225], v[32:35]
	ds_read_b128 v[222:225], v6 offset:12288
	s_waitcnt lgkmcnt(3)
	v_mfma_f32_16x16x32_bf16 v[88:91], v[158:161], v[226:229], v[88:91]
	s_mov_b32 m0, s41
	v_mfma_f32_16x16x32_bf16 v[92:95], v[166:169], v[226:229], v[92:95]
	global_load_lds_dwordx4 v2, s[50:51]
	v_mfma_f32_16x16x32_bf16 v[96:99], v[214:217], v[226:229], v[96:99]
	v_mfma_f32_16x16x32_bf16 v[36:39], v[218:221], v[226:229], v[36:39]
	ds_read_b128 v[226:229], v6 offset:14336
	s_waitcnt lgkmcnt(3)
	v_mfma_f32_16x16x32_bf16 v[104:107], v[158:161], v[162:165], v[104:107]
	s_waitcnt lgkmcnt(2)
	v_mfma_f32_16x16x32_bf16 v[116:119], v[158:161], v[178:181], v[116:119]
	s_waitcnt lgkmcnt(1)
	s_mov_b32 m0, s42
	v_mfma_f32_16x16x32_bf16 v[128:131], v[158:161], v[222:225], v[128:131]
	global_load_lds_dwordx4 v2, s[52:53]
	s_waitcnt lgkmcnt(0)
	v_mfma_f32_16x16x32_bf16 v[100:103], v[158:161], v[226:229], v[100:103]
	ds_read_b128 v[158:161], v7 offset:33792
	v_mfma_f32_16x16x32_bf16 v[108:111], v[166:169], v[162:165], v[108:111]
	v_mfma_f32_16x16x32_bf16 v[120:123], v[166:169], v[178:181], v[120:123]
	v_mfma_f32_16x16x32_bf16 v[132:135], v[166:169], v[222:225], v[132:135]
	s_mov_b32 m0, s43
	v_mfma_f32_16x16x32_bf16 v[140:143], v[166:169], v[226:229], v[140:143]
	global_load_lds_dwordx4 v4, s[50:51]
	ds_read_b128 v[166:169], v6 offset:1024
	v_mfma_f32_16x16x32_bf16 v[112:115], v[214:217], v[162:165], v[112:115]
	v_mfma_f32_16x16x32_bf16 v[52:55], v[218:221], v[162:165], v[52:55]
	ds_read_b128 v[162:165], v7 offset:35840
	v_mfma_f32_16x16x32_bf16 v[124:127], v[214:217], v[178:181], v[124:127]
	v_mfma_f32_16x16x32_bf16 v[68:71], v[218:221], v[178:181], v[68:71]
	ds_read_b128 v[178:181], v6 offset:3072
	s_mov_b32 m0, s44
	v_mfma_f32_16x16x32_bf16 v[136:139], v[214:217], v[222:225], v[136:139]
	global_load_lds_dwordx4 v4, s[52:53]
	v_mfma_f32_16x16x32_bf16 v[84:87], v[218:221], v[222:225], v[84:87]
	ds_read_b128 v[222:225], v6 offset:5120
	v_mfma_f32_16x16x32_bf16 v[150:153], v[214:217], v[226:229], v[150:153]
	ds_read_b128 v[214:217], v7 offset:37888
	v_mfma_f32_16x16x32_bf16 v[154:157], v[218:221], v[226:229], v[154:157]
	ds_read_b128 v[218:221], v7 offset:39936
	ds_read_b128 v[226:229], v6 offset:7168
	s_waitcnt lgkmcnt(6)
	v_mfma_f32_16x16x32_bf16 v[40:43], v[158:161], v[166:169], v[40:43]
	s_waitcnt lgkmcnt(5)
	s_mov_b32 m0, s45
	v_mfma_f32_16x16x32_bf16 v[44:47], v[162:165], v[166:169], v[44:47]
	global_load_lds_dwordx4 v146, s[50:51]
	s_waitcnt lgkmcnt(4)
	v_mfma_f32_16x16x32_bf16 v[56:59], v[158:161], v[178:181], v[56:59]
	v_mfma_f32_16x16x32_bf16 v[60:63], v[162:165], v[178:181], v[60:63]
	s_waitcnt lgkmcnt(3)
	v_mfma_f32_16x16x32_bf16 v[72:75], v[158:161], v[222:225], v[72:75]
	v_mfma_f32_16x16x32_bf16 v[76:79], v[162:165], v[222:225], v[76:79]
	s_waitcnt lgkmcnt(2)
	s_mov_b32 m0, s46
	v_mfma_f32_16x16x32_bf16 v[48:51], v[214:217], v[166:169], v[48:51]
	global_load_lds_dwordx4 v146, s[52:53]
	s_waitcnt lgkmcnt(1)
	v_mfma_f32_16x16x32_bf16 v[174:177], v[218:221], v[166:169], v[174:177]
	ds_read_b128 v[166:169], v6 offset:9216
	v_mfma_f32_16x16x32_bf16 v[64:67], v[214:217], v[178:181], v[64:67]
	v_mfma_f32_16x16x32_bf16 v[170:173], v[218:221], v[178:181], v[170:173]
	ds_read_b128 v[178:181], v6 offset:11264
	v_mfma_f32_16x16x32_bf16 v[80:83], v[214:217], v[222:225], v[80:83]
	v_mfma_f32_16x16x32_bf16 v[32:35], v[218:221], v[222:225], v[32:35]
	ds_read_b128 v[222:225], v6 offset:13312
	s_waitcnt lgkmcnt(3)
	v_mfma_f32_16x16x32_bf16 v[88:91], v[158:161], v[226:229], v[88:91]
	v_mfma_f32_16x16x32_bf16 v[92:95], v[162:165], v[226:229], v[92:95]
	v_mfma_f32_16x16x32_bf16 v[96:99], v[214:217], v[226:229], v[96:99]
	v_mfma_f32_16x16x32_bf16 v[36:39], v[218:221], v[226:229], v[36:39]
	ds_read_b128 v[226:229], v6 offset:15360
	s_waitcnt lgkmcnt(3)
	v_mfma_f32_16x16x32_bf16 v[104:107], v[158:161], v[166:169], v[104:107]
	v_mfma_f32_16x16x32_bf16 v[108:111], v[162:165], v[166:169], v[108:111]
	v_mfma_f32_16x16x32_bf16 v[112:115], v[214:217], v[166:169], v[112:115]
	v_mfma_f32_16x16x32_bf16 v[52:55], v[218:221], v[166:169], v[52:55]
	s_waitcnt lgkmcnt(2)
	v_mfma_f32_16x16x32_bf16 v[116:119], v[158:161], v[178:181], v[116:119]
	v_mfma_f32_16x16x32_bf16 v[120:123], v[162:165], v[178:181], v[120:123]
	v_mfma_f32_16x16x32_bf16 v[124:127], v[214:217], v[178:181], v[124:127]
	v_mfma_f32_16x16x32_bf16 v[68:71], v[218:221], v[178:181], v[68:71]
	s_waitcnt lgkmcnt(1)
	v_mfma_f32_16x16x32_bf16 v[128:131], v[158:161], v[222:225], v[128:131]
	v_mfma_f32_16x16x32_bf16 v[132:135], v[162:165], v[222:225], v[132:135]
	v_mfma_f32_16x16x32_bf16 v[136:139], v[214:217], v[222:225], v[136:139]
	v_mfma_f32_16x16x32_bf16 v[84:87], v[218:221], v[222:225], v[84:87]
	s_waitcnt lgkmcnt(0)
	v_mfma_f32_16x16x32_bf16 v[100:103], v[158:161], v[226:229], v[100:103]
	v_mfma_f32_16x16x32_bf16 v[140:143], v[162:165], v[226:229], v[140:143]
	v_mfma_f32_16x16x32_bf16 v[150:153], v[214:217], v[226:229], v[150:153]
	v_mfma_f32_16x16x32_bf16 v[154:157], v[218:221], v[226:229], v[154:157]
	s_add_u32 s50, s14, 0xb00
	s_addc_u32 s51, s15, 0
	s_add_u32 s52, s20, 0xb00
	s_waitcnt vmcnt(0)
	s_barrier
	s_addc_u32 s53, s21, 0
	ds_read_b128 v[158:161], v8
	ds_read_b128 v[162:165], v12
	ds_read_b128 v[166:169], v9
	ds_read_b128 v[178:181], v13
	ds_read_b128 v[214:217], v11
	ds_read_b128 v[218:221], v10
	ds_read_b128 v[222:225], v14
	ds_read_b128 v[226:229], v15
	s_waitcnt lgkmcnt(6)
	v_mfma_f32_16x16x32_bf16 v[40:43], v[158:161], v[162:165], v[40:43]
	s_waitcnt lgkmcnt(5)
	v_mfma_f32_16x16x32_bf16 v[44:47], v[166:169], v[162:165], v[44:47]
	s_waitcnt lgkmcnt(4)
	v_mfma_f32_16x16x32_bf16 v[56:59], v[158:161], v[178:181], v[56:59]
	s_mov_b32 m0, s1
	v_mfma_f32_16x16x32_bf16 v[60:63], v[166:169], v[178:181], v[60:63]
	global_load_lds_dwordx4 v0, s[50:51]
	s_waitcnt lgkmcnt(3)
	v_mfma_f32_16x16x32_bf16 v[48:51], v[214:217], v[162:165], v[48:51]
	v_mfma_f32_16x16x32_bf16 v[64:67], v[214:217], v[178:181], v[64:67]
	s_waitcnt lgkmcnt(2)
	v_mfma_f32_16x16x32_bf16 v[174:177], v[218:221], v[162:165], v[174:177]
	ds_read_b128 v[162:165], v16
	v_mfma_f32_16x16x32_bf16 v[170:173], v[218:221], v[178:181], v[170:173]
	ds_read_b128 v[178:181], v17
	s_waitcnt lgkmcnt(3)
	s_mov_b32 m0, s34
	v_mfma_f32_16x16x32_bf16 v[72:75], v[158:161], v[222:225], v[72:75]
	global_load_lds_dwordx4 v0, s[52:53]
	v_mfma_f32_16x16x32_bf16 v[76:79], v[166:169], v[222:225], v[76:79]
	v_mfma_f32_16x16x32_bf16 v[80:83], v[214:217], v[222:225], v[80:83]
	v_mfma_f32_16x16x32_bf16 v[32:35], v[218:221], v[222:225], v[32:35]
	ds_read_b128 v[222:225], v18
	s_waitcnt lgkmcnt(3)
	v_mfma_f32_16x16x32_bf16 v[88:91], v[158:161], v[226:229], v[88:91]
	s_mov_b32 m0, s35
	v_mfma_f32_16x16x32_bf16 v[92:95], v[166:169], v[226:229], v[92:95]
	global_load_lds_dwordx4 v2, s[50:51]
	v_mfma_f32_16x16x32_bf16 v[96:99], v[214:217], v[226:229], v[96:99]
	v_mfma_f32_16x16x32_bf16 v[36:39], v[218:221], v[226:229], v[36:39]
	ds_read_b128 v[226:229], v19
	s_waitcnt lgkmcnt(3)
	v_mfma_f32_16x16x32_bf16 v[104:107], v[158:161], v[162:165], v[104:107]
	s_waitcnt lgkmcnt(2)
	v_mfma_f32_16x16x32_bf16 v[116:119], v[158:161], v[178:181], v[116:119]
	s_waitcnt lgkmcnt(1)
	s_mov_b32 m0, s36
	v_mfma_f32_16x16x32_bf16 v[128:131], v[158:161], v[222:225], v[128:131]
	global_load_lds_dwordx4 v2, s[52:53]
	s_waitcnt lgkmcnt(0)
	v_mfma_f32_16x16x32_bf16 v[100:103], v[158:161], v[226:229], v[100:103]
	ds_read_b128 v[158:161], v20
	v_mfma_f32_16x16x32_bf16 v[108:111], v[166:169], v[162:165], v[108:111]
	v_mfma_f32_16x16x32_bf16 v[120:123], v[166:169], v[178:181], v[120:123]
	v_mfma_f32_16x16x32_bf16 v[132:135], v[166:169], v[222:225], v[132:135]
	s_mov_b32 m0, s37
	v_mfma_f32_16x16x32_bf16 v[140:143], v[166:169], v[226:229], v[140:143]
	global_load_lds_dwordx4 v4, s[50:51]
	ds_read_b128 v[166:169], v24
	v_mfma_f32_16x16x32_bf16 v[112:115], v[214:217], v[162:165], v[112:115]
	v_mfma_f32_16x16x32_bf16 v[52:55], v[218:221], v[162:165], v[52:55]
	ds_read_b128 v[162:165], v21
	v_mfma_f32_16x16x32_bf16 v[124:127], v[214:217], v[178:181], v[124:127]
	v_mfma_f32_16x16x32_bf16 v[68:71], v[218:221], v[178:181], v[68:71]
	ds_read_b128 v[178:181], v25
	s_mov_b32 m0, s38
	v_mfma_f32_16x16x32_bf16 v[136:139], v[214:217], v[222:225], v[136:139]
	global_load_lds_dwordx4 v4, s[52:53]
	v_mfma_f32_16x16x32_bf16 v[84:87], v[218:221], v[222:225], v[84:87]
	ds_read_b128 v[222:225], v26
	v_mfma_f32_16x16x32_bf16 v[150:153], v[214:217], v[226:229], v[150:153]
	ds_read_b128 v[214:217], v23
	v_mfma_f32_16x16x32_bf16 v[154:157], v[218:221], v[226:229], v[154:157]
	ds_read_b128 v[218:221], v22
	ds_read_b128 v[226:229], v27
	s_waitcnt lgkmcnt(6)
	v_mfma_f32_16x16x32_bf16 v[40:43], v[158:161], v[166:169], v[40:43]
	s_waitcnt lgkmcnt(5)
	s_mov_b32 m0, s39
	v_mfma_f32_16x16x32_bf16 v[44:47], v[162:165], v[166:169], v[44:47]
	global_load_lds_dwordx4 v146, s[50:51]
	s_waitcnt lgkmcnt(4)
	v_mfma_f32_16x16x32_bf16 v[56:59], v[158:161], v[178:181], v[56:59]
	v_mfma_f32_16x16x32_bf16 v[60:63], v[162:165], v[178:181], v[60:63]
	s_waitcnt lgkmcnt(3)
	v_mfma_f32_16x16x32_bf16 v[72:75], v[158:161], v[222:225], v[72:75]
	v_mfma_f32_16x16x32_bf16 v[76:79], v[162:165], v[222:225], v[76:79]
	s_waitcnt lgkmcnt(2)
	s_mov_b32 m0, s40
	v_mfma_f32_16x16x32_bf16 v[48:51], v[214:217], v[166:169], v[48:51]
	global_load_lds_dwordx4 v146, s[52:53]
	s_waitcnt lgkmcnt(1)
	v_mfma_f32_16x16x32_bf16 v[174:177], v[218:221], v[166:169], v[174:177]
	ds_read_b128 v[166:169], v28
	v_mfma_f32_16x16x32_bf16 v[64:67], v[214:217], v[178:181], v[64:67]
	v_mfma_f32_16x16x32_bf16 v[170:173], v[218:221], v[178:181], v[170:173]
	ds_read_b128 v[178:181], v29
	v_mfma_f32_16x16x32_bf16 v[80:83], v[214:217], v[222:225], v[80:83]
	v_mfma_f32_16x16x32_bf16 v[32:35], v[218:221], v[222:225], v[32:35]
	ds_read_b128 v[222:225], v30
	s_waitcnt lgkmcnt(3)
	v_mfma_f32_16x16x32_bf16 v[88:91], v[158:161], v[226:229], v[88:91]
	v_mfma_f32_16x16x32_bf16 v[92:95], v[162:165], v[226:229], v[92:95]
	v_mfma_f32_16x16x32_bf16 v[96:99], v[214:217], v[226:229], v[96:99]
	v_mfma_f32_16x16x32_bf16 v[36:39], v[218:221], v[226:229], v[36:39]
	ds_read_b128 v[226:229], v31
	s_waitcnt lgkmcnt(3)
	v_mfma_f32_16x16x32_bf16 v[104:107], v[158:161], v[166:169], v[104:107]
	v_mfma_f32_16x16x32_bf16 v[108:111], v[162:165], v[166:169], v[108:111]
	v_mfma_f32_16x16x32_bf16 v[112:115], v[214:217], v[166:169], v[112:115]
	v_mfma_f32_16x16x32_bf16 v[52:55], v[218:221], v[166:169], v[52:55]
	s_waitcnt lgkmcnt(2)
	v_mfma_f32_16x16x32_bf16 v[116:119], v[158:161], v[178:181], v[116:119]
	v_mfma_f32_16x16x32_bf16 v[120:123], v[162:165], v[178:181], v[120:123]
	v_mfma_f32_16x16x32_bf16 v[124:127], v[214:217], v[178:181], v[124:127]
	v_mfma_f32_16x16x32_bf16 v[68:71], v[218:221], v[178:181], v[68:71]
	s_waitcnt lgkmcnt(1)
	v_mfma_f32_16x16x32_bf16 v[128:131], v[158:161], v[222:225], v[128:131]
	v_mfma_f32_16x16x32_bf16 v[132:135], v[162:165], v[222:225], v[132:135]
	v_mfma_f32_16x16x32_bf16 v[136:139], v[214:217], v[222:225], v[136:139]
	v_mfma_f32_16x16x32_bf16 v[84:87], v[218:221], v[222:225], v[84:87]
	s_waitcnt lgkmcnt(0)
	v_mfma_f32_16x16x32_bf16 v[100:103], v[158:161], v[226:229], v[100:103]
	v_mfma_f32_16x16x32_bf16 v[140:143], v[162:165], v[226:229], v[140:143]
	v_mfma_f32_16x16x32_bf16 v[150:153], v[214:217], v[226:229], v[150:153]
	v_mfma_f32_16x16x32_bf16 v[154:157], v[218:221], v[226:229], v[154:157]
	s_add_u32 s50, s14, 0xb80
	s_addc_u32 s51, s15, 0
	s_add_u32 s52, s20, 0xb80
	s_waitcnt vmcnt(0)
	s_barrier
	s_addc_u32 s53, s21, 0
	ds_read_b128 v[158:161], v7 offset:32768
	ds_read_b128 v[162:165], v6
	ds_read_b128 v[166:169], v7 offset:34816
	ds_read_b128 v[178:181], v6 offset:2048
	ds_read_b128 v[214:217], v7 offset:36864
	ds_read_b128 v[218:221], v7 offset:38912
	ds_read_b128 v[222:225], v6 offset:4096
	ds_read_b128 v[226:229], v6 offset:6144
	s_waitcnt lgkmcnt(6)
	v_mfma_f32_16x16x32_bf16 v[40:43], v[158:161], v[162:165], v[40:43]
	s_waitcnt lgkmcnt(5)
	v_mfma_f32_16x16x32_bf16 v[44:47], v[166:169], v[162:165], v[44:47]
	s_waitcnt lgkmcnt(4)
	v_mfma_f32_16x16x32_bf16 v[56:59], v[158:161], v[178:181], v[56:59]
	s_mov_b32 m0, s27
	v_mfma_f32_16x16x32_bf16 v[60:63], v[166:169], v[178:181], v[60:63]
	global_load_lds_dwordx4 v0, s[50:51]
	s_waitcnt lgkmcnt(3)
	v_mfma_f32_16x16x32_bf16 v[48:51], v[214:217], v[162:165], v[48:51]
	v_mfma_f32_16x16x32_bf16 v[64:67], v[214:217], v[178:181], v[64:67]
	s_waitcnt lgkmcnt(2)
	v_mfma_f32_16x16x32_bf16 v[174:177], v[218:221], v[162:165], v[174:177]
	ds_read_b128 v[162:165], v6 offset:8192
	v_mfma_f32_16x16x32_bf16 v[170:173], v[218:221], v[178:181], v[170:173]
	ds_read_b128 v[178:181], v6 offset:10240
	s_waitcnt lgkmcnt(3)
	s_mov_b32 m0, s26
	v_mfma_f32_16x16x32_bf16 v[72:75], v[158:161], v[222:225], v[72:75]
	global_load_lds_dwordx4 v0, s[52:53]
	v_mfma_f32_16x16x32_bf16 v[76:79], v[166:169], v[222:225], v[76:79]
	v_mfma_f32_16x16x32_bf16 v[80:83], v[214:217], v[222:225], v[80:83]
	v_mfma_f32_16x16x32_bf16 v[32:35], v[218:221], v[222:225], v[32:35]
	ds_read_b128 v[222:225], v6 offset:12288
	s_waitcnt lgkmcnt(3)
	v_mfma_f32_16x16x32_bf16 v[88:91], v[158:161], v[226:229], v[88:91]
	s_mov_b32 m0, s41
	v_mfma_f32_16x16x32_bf16 v[92:95], v[166:169], v[226:229], v[92:95]
	global_load_lds_dwordx4 v2, s[50:51]
	v_mfma_f32_16x16x32_bf16 v[96:99], v[214:217], v[226:229], v[96:99]
	v_mfma_f32_16x16x32_bf16 v[36:39], v[218:221], v[226:229], v[36:39]
	ds_read_b128 v[226:229], v6 offset:14336
	s_waitcnt lgkmcnt(3)
	v_mfma_f32_16x16x32_bf16 v[104:107], v[158:161], v[162:165], v[104:107]
	s_waitcnt lgkmcnt(2)
	v_mfma_f32_16x16x32_bf16 v[116:119], v[158:161], v[178:181], v[116:119]
	s_waitcnt lgkmcnt(1)
	s_mov_b32 m0, s42
	v_mfma_f32_16x16x32_bf16 v[128:131], v[158:161], v[222:225], v[128:131]
	global_load_lds_dwordx4 v2, s[52:53]
	s_waitcnt lgkmcnt(0)
	v_mfma_f32_16x16x32_bf16 v[100:103], v[158:161], v[226:229], v[100:103]
	ds_read_b128 v[158:161], v7 offset:33792
	v_mfma_f32_16x16x32_bf16 v[108:111], v[166:169], v[162:165], v[108:111]
	v_mfma_f32_16x16x32_bf16 v[120:123], v[166:169], v[178:181], v[120:123]
	v_mfma_f32_16x16x32_bf16 v[132:135], v[166:169], v[222:225], v[132:135]
	s_mov_b32 m0, s43
	v_mfma_f32_16x16x32_bf16 v[140:143], v[166:169], v[226:229], v[140:143]
	global_load_lds_dwordx4 v4, s[50:51]
	ds_read_b128 v[166:169], v6 offset:1024
	v_mfma_f32_16x16x32_bf16 v[112:115], v[214:217], v[162:165], v[112:115]
	v_mfma_f32_16x16x32_bf16 v[52:55], v[218:221], v[162:165], v[52:55]
	ds_read_b128 v[162:165], v7 offset:35840
	v_mfma_f32_16x16x32_bf16 v[124:127], v[214:217], v[178:181], v[124:127]
	v_mfma_f32_16x16x32_bf16 v[68:71], v[218:221], v[178:181], v[68:71]
	ds_read_b128 v[178:181], v6 offset:3072
	s_mov_b32 m0, s44
	v_mfma_f32_16x16x32_bf16 v[136:139], v[214:217], v[222:225], v[136:139]
	global_load_lds_dwordx4 v4, s[52:53]
	v_mfma_f32_16x16x32_bf16 v[84:87], v[218:221], v[222:225], v[84:87]
	ds_read_b128 v[222:225], v6 offset:5120
	v_mfma_f32_16x16x32_bf16 v[150:153], v[214:217], v[226:229], v[150:153]
	ds_read_b128 v[214:217], v7 offset:37888
	v_mfma_f32_16x16x32_bf16 v[154:157], v[218:221], v[226:229], v[154:157]
	ds_read_b128 v[218:221], v7 offset:39936
	ds_read_b128 v[226:229], v6 offset:7168
	s_waitcnt lgkmcnt(6)
	v_mfma_f32_16x16x32_bf16 v[40:43], v[158:161], v[166:169], v[40:43]
	s_waitcnt lgkmcnt(5)
	s_mov_b32 m0, s45
	v_mfma_f32_16x16x32_bf16 v[44:47], v[162:165], v[166:169], v[44:47]
	global_load_lds_dwordx4 v146, s[50:51]
	s_waitcnt lgkmcnt(4)
	v_mfma_f32_16x16x32_bf16 v[56:59], v[158:161], v[178:181], v[56:59]
	v_mfma_f32_16x16x32_bf16 v[60:63], v[162:165], v[178:181], v[60:63]
	s_waitcnt lgkmcnt(3)
	v_mfma_f32_16x16x32_bf16 v[72:75], v[158:161], v[222:225], v[72:75]
	v_mfma_f32_16x16x32_bf16 v[76:79], v[162:165], v[222:225], v[76:79]
	s_waitcnt lgkmcnt(2)
	s_mov_b32 m0, s46
	v_mfma_f32_16x16x32_bf16 v[48:51], v[214:217], v[166:169], v[48:51]
	global_load_lds_dwordx4 v146, s[52:53]
	s_waitcnt lgkmcnt(1)
	v_mfma_f32_16x16x32_bf16 v[174:177], v[218:221], v[166:169], v[174:177]
	ds_read_b128 v[166:169], v6 offset:9216
	v_mfma_f32_16x16x32_bf16 v[64:67], v[214:217], v[178:181], v[64:67]
	v_mfma_f32_16x16x32_bf16 v[170:173], v[218:221], v[178:181], v[170:173]
	ds_read_b128 v[178:181], v6 offset:11264
	v_mfma_f32_16x16x32_bf16 v[80:83], v[214:217], v[222:225], v[80:83]
	v_mfma_f32_16x16x32_bf16 v[32:35], v[218:221], v[222:225], v[32:35]
	ds_read_b128 v[222:225], v6 offset:13312
	s_waitcnt lgkmcnt(3)
	v_mfma_f32_16x16x32_bf16 v[88:91], v[158:161], v[226:229], v[88:91]
	v_mfma_f32_16x16x32_bf16 v[92:95], v[162:165], v[226:229], v[92:95]
	v_mfma_f32_16x16x32_bf16 v[96:99], v[214:217], v[226:229], v[96:99]
	v_mfma_f32_16x16x32_bf16 v[36:39], v[218:221], v[226:229], v[36:39]
	ds_read_b128 v[226:229], v6 offset:15360
	s_waitcnt lgkmcnt(3)
	v_mfma_f32_16x16x32_bf16 v[104:107], v[158:161], v[166:169], v[104:107]
	v_mfma_f32_16x16x32_bf16 v[108:111], v[162:165], v[166:169], v[108:111]
	v_mfma_f32_16x16x32_bf16 v[112:115], v[214:217], v[166:169], v[112:115]
	v_mfma_f32_16x16x32_bf16 v[52:55], v[218:221], v[166:169], v[52:55]
	s_waitcnt lgkmcnt(2)
	v_mfma_f32_16x16x32_bf16 v[116:119], v[158:161], v[178:181], v[116:119]
	v_mfma_f32_16x16x32_bf16 v[120:123], v[162:165], v[178:181], v[120:123]
	v_mfma_f32_16x16x32_bf16 v[124:127], v[214:217], v[178:181], v[124:127]
	v_mfma_f32_16x16x32_bf16 v[68:71], v[218:221], v[178:181], v[68:71]
	s_waitcnt lgkmcnt(1)
	v_mfma_f32_16x16x32_bf16 v[128:131], v[158:161], v[222:225], v[128:131]
	v_mfma_f32_16x16x32_bf16 v[132:135], v[162:165], v[222:225], v[132:135]
	v_mfma_f32_16x16x32_bf16 v[136:139], v[214:217], v[222:225], v[136:139]
	v_mfma_f32_16x16x32_bf16 v[84:87], v[218:221], v[222:225], v[84:87]
	s_waitcnt lgkmcnt(0)
	v_mfma_f32_16x16x32_bf16 v[100:103], v[158:161], v[226:229], v[100:103]
	v_mfma_f32_16x16x32_bf16 v[140:143], v[162:165], v[226:229], v[140:143]
	v_mfma_f32_16x16x32_bf16 v[150:153], v[214:217], v[226:229], v[150:153]
	v_mfma_f32_16x16x32_bf16 v[154:157], v[218:221], v[226:229], v[154:157]
	s_add_u32 s50, s14, 0xc00
	s_addc_u32 s51, s15, 0
	s_add_u32 s52, s20, 0xc00
	s_waitcnt vmcnt(0)
	s_barrier
	s_addc_u32 s53, s21, 0
	ds_read_b128 v[158:161], v8
	ds_read_b128 v[162:165], v12
	ds_read_b128 v[166:169], v9
	ds_read_b128 v[178:181], v13
	ds_read_b128 v[214:217], v11
	ds_read_b128 v[218:221], v10
	ds_read_b128 v[222:225], v14
	ds_read_b128 v[226:229], v15
	s_waitcnt lgkmcnt(6)
	v_mfma_f32_16x16x32_bf16 v[40:43], v[158:161], v[162:165], v[40:43]
	s_waitcnt lgkmcnt(5)
	v_mfma_f32_16x16x32_bf16 v[44:47], v[166:169], v[162:165], v[44:47]
	s_waitcnt lgkmcnt(4)
	v_mfma_f32_16x16x32_bf16 v[56:59], v[158:161], v[178:181], v[56:59]
	s_mov_b32 m0, s1
	v_mfma_f32_16x16x32_bf16 v[60:63], v[166:169], v[178:181], v[60:63]
	global_load_lds_dwordx4 v0, s[50:51]
	s_waitcnt lgkmcnt(3)
	v_mfma_f32_16x16x32_bf16 v[48:51], v[214:217], v[162:165], v[48:51]
	v_mfma_f32_16x16x32_bf16 v[64:67], v[214:217], v[178:181], v[64:67]
	s_waitcnt lgkmcnt(2)
	v_mfma_f32_16x16x32_bf16 v[174:177], v[218:221], v[162:165], v[174:177]
	ds_read_b128 v[162:165], v16
	v_mfma_f32_16x16x32_bf16 v[170:173], v[218:221], v[178:181], v[170:173]
	ds_read_b128 v[178:181], v17
	s_waitcnt lgkmcnt(3)
	s_mov_b32 m0, s34
	v_mfma_f32_16x16x32_bf16 v[72:75], v[158:161], v[222:225], v[72:75]
	global_load_lds_dwordx4 v0, s[52:53]
	v_mfma_f32_16x16x32_bf16 v[76:79], v[166:169], v[222:225], v[76:79]
	v_mfma_f32_16x16x32_bf16 v[80:83], v[214:217], v[222:225], v[80:83]
	v_mfma_f32_16x16x32_bf16 v[32:35], v[218:221], v[222:225], v[32:35]
	ds_read_b128 v[222:225], v18
	s_waitcnt lgkmcnt(3)
	v_mfma_f32_16x16x32_bf16 v[88:91], v[158:161], v[226:229], v[88:91]
	s_mov_b32 m0, s35
	v_mfma_f32_16x16x32_bf16 v[92:95], v[166:169], v[226:229], v[92:95]
	global_load_lds_dwordx4 v2, s[50:51]
	v_mfma_f32_16x16x32_bf16 v[96:99], v[214:217], v[226:229], v[96:99]
	v_mfma_f32_16x16x32_bf16 v[36:39], v[218:221], v[226:229], v[36:39]
	ds_read_b128 v[226:229], v19
	s_waitcnt lgkmcnt(3)
	v_mfma_f32_16x16x32_bf16 v[104:107], v[158:161], v[162:165], v[104:107]
	s_waitcnt lgkmcnt(2)
	v_mfma_f32_16x16x32_bf16 v[116:119], v[158:161], v[178:181], v[116:119]
	s_waitcnt lgkmcnt(1)
	s_mov_b32 m0, s36
	v_mfma_f32_16x16x32_bf16 v[128:131], v[158:161], v[222:225], v[128:131]
	global_load_lds_dwordx4 v2, s[52:53]
	s_waitcnt lgkmcnt(0)
	v_mfma_f32_16x16x32_bf16 v[100:103], v[158:161], v[226:229], v[100:103]
	ds_read_b128 v[158:161], v20
	v_mfma_f32_16x16x32_bf16 v[108:111], v[166:169], v[162:165], v[108:111]
	v_mfma_f32_16x16x32_bf16 v[120:123], v[166:169], v[178:181], v[120:123]
	v_mfma_f32_16x16x32_bf16 v[132:135], v[166:169], v[222:225], v[132:135]
	s_mov_b32 m0, s37
	v_mfma_f32_16x16x32_bf16 v[140:143], v[166:169], v[226:229], v[140:143]
	global_load_lds_dwordx4 v4, s[50:51]
	ds_read_b128 v[166:169], v24
	v_mfma_f32_16x16x32_bf16 v[112:115], v[214:217], v[162:165], v[112:115]
	v_mfma_f32_16x16x32_bf16 v[52:55], v[218:221], v[162:165], v[52:55]
	ds_read_b128 v[162:165], v21
	v_mfma_f32_16x16x32_bf16 v[124:127], v[214:217], v[178:181], v[124:127]
	v_mfma_f32_16x16x32_bf16 v[68:71], v[218:221], v[178:181], v[68:71]
	ds_read_b128 v[178:181], v25
	s_mov_b32 m0, s38
	v_mfma_f32_16x16x32_bf16 v[136:139], v[214:217], v[222:225], v[136:139]
	global_load_lds_dwordx4 v4, s[52:53]
	v_mfma_f32_16x16x32_bf16 v[84:87], v[218:221], v[222:225], v[84:87]
	ds_read_b128 v[222:225], v26
	v_mfma_f32_16x16x32_bf16 v[150:153], v[214:217], v[226:229], v[150:153]
	ds_read_b128 v[214:217], v23
	v_mfma_f32_16x16x32_bf16 v[154:157], v[218:221], v[226:229], v[154:157]
	ds_read_b128 v[218:221], v22
	ds_read_b128 v[226:229], v27
	s_waitcnt lgkmcnt(6)
	v_mfma_f32_16x16x32_bf16 v[40:43], v[158:161], v[166:169], v[40:43]
	s_waitcnt lgkmcnt(5)
	s_mov_b32 m0, s39
	v_mfma_f32_16x16x32_bf16 v[44:47], v[162:165], v[166:169], v[44:47]
	global_load_lds_dwordx4 v146, s[50:51]
	s_waitcnt lgkmcnt(4)
	v_mfma_f32_16x16x32_bf16 v[56:59], v[158:161], v[178:181], v[56:59]
	v_mfma_f32_16x16x32_bf16 v[60:63], v[162:165], v[178:181], v[60:63]
	s_waitcnt lgkmcnt(3)
	v_mfma_f32_16x16x32_bf16 v[72:75], v[158:161], v[222:225], v[72:75]
	v_mfma_f32_16x16x32_bf16 v[76:79], v[162:165], v[222:225], v[76:79]
	s_waitcnt lgkmcnt(2)
	s_mov_b32 m0, s40
	v_mfma_f32_16x16x32_bf16 v[48:51], v[214:217], v[166:169], v[48:51]
	global_load_lds_dwordx4 v146, s[52:53]
	s_waitcnt lgkmcnt(1)
	v_mfma_f32_16x16x32_bf16 v[174:177], v[218:221], v[166:169], v[174:177]
	ds_read_b128 v[166:169], v28
	v_mfma_f32_16x16x32_bf16 v[64:67], v[214:217], v[178:181], v[64:67]
	v_mfma_f32_16x16x32_bf16 v[170:173], v[218:221], v[178:181], v[170:173]
	ds_read_b128 v[178:181], v29
	v_mfma_f32_16x16x32_bf16 v[80:83], v[214:217], v[222:225], v[80:83]
	v_mfma_f32_16x16x32_bf16 v[32:35], v[218:221], v[222:225], v[32:35]
	ds_read_b128 v[222:225], v30
	s_waitcnt lgkmcnt(3)
	v_mfma_f32_16x16x32_bf16 v[88:91], v[158:161], v[226:229], v[88:91]
	v_mfma_f32_16x16x32_bf16 v[92:95], v[162:165], v[226:229], v[92:95]
	v_mfma_f32_16x16x32_bf16 v[96:99], v[214:217], v[226:229], v[96:99]
	v_mfma_f32_16x16x32_bf16 v[36:39], v[218:221], v[226:229], v[36:39]
	ds_read_b128 v[226:229], v31
	s_waitcnt lgkmcnt(3)
	v_mfma_f32_16x16x32_bf16 v[104:107], v[158:161], v[166:169], v[104:107]
	v_mfma_f32_16x16x32_bf16 v[108:111], v[162:165], v[166:169], v[108:111]
	v_mfma_f32_16x16x32_bf16 v[112:115], v[214:217], v[166:169], v[112:115]
	v_mfma_f32_16x16x32_bf16 v[52:55], v[218:221], v[166:169], v[52:55]
	s_waitcnt lgkmcnt(2)
	v_mfma_f32_16x16x32_bf16 v[116:119], v[158:161], v[178:181], v[116:119]
	v_mfma_f32_16x16x32_bf16 v[120:123], v[162:165], v[178:181], v[120:123]
	v_mfma_f32_16x16x32_bf16 v[124:127], v[214:217], v[178:181], v[124:127]
	v_mfma_f32_16x16x32_bf16 v[68:71], v[218:221], v[178:181], v[68:71]
	s_waitcnt lgkmcnt(1)
	v_mfma_f32_16x16x32_bf16 v[128:131], v[158:161], v[222:225], v[128:131]
	v_mfma_f32_16x16x32_bf16 v[132:135], v[162:165], v[222:225], v[132:135]
	v_mfma_f32_16x16x32_bf16 v[136:139], v[214:217], v[222:225], v[136:139]
	v_mfma_f32_16x16x32_bf16 v[84:87], v[218:221], v[222:225], v[84:87]
	s_waitcnt lgkmcnt(0)
	v_mfma_f32_16x16x32_bf16 v[100:103], v[158:161], v[226:229], v[100:103]
	v_mfma_f32_16x16x32_bf16 v[140:143], v[162:165], v[226:229], v[140:143]
	v_mfma_f32_16x16x32_bf16 v[150:153], v[214:217], v[226:229], v[150:153]
	v_mfma_f32_16x16x32_bf16 v[154:157], v[218:221], v[226:229], v[154:157]
	s_add_u32 s50, s14, 0xc80
	s_addc_u32 s51, s15, 0
	s_add_u32 s52, s20, 0xc80
	s_waitcnt vmcnt(0)
	s_barrier
	s_addc_u32 s53, s21, 0
	ds_read_b128 v[158:161], v7 offset:32768
	ds_read_b128 v[162:165], v6
	ds_read_b128 v[166:169], v7 offset:34816
	ds_read_b128 v[178:181], v6 offset:2048
	ds_read_b128 v[214:217], v7 offset:36864
	ds_read_b128 v[218:221], v7 offset:38912
	ds_read_b128 v[222:225], v6 offset:4096
	ds_read_b128 v[226:229], v6 offset:6144
	s_waitcnt lgkmcnt(6)
	v_mfma_f32_16x16x32_bf16 v[40:43], v[158:161], v[162:165], v[40:43]
	s_waitcnt lgkmcnt(5)
	v_mfma_f32_16x16x32_bf16 v[44:47], v[166:169], v[162:165], v[44:47]
	s_waitcnt lgkmcnt(4)
	v_mfma_f32_16x16x32_bf16 v[56:59], v[158:161], v[178:181], v[56:59]
	s_mov_b32 m0, s27
	v_mfma_f32_16x16x32_bf16 v[60:63], v[166:169], v[178:181], v[60:63]
	global_load_lds_dwordx4 v0, s[50:51]
	s_waitcnt lgkmcnt(3)
	v_mfma_f32_16x16x32_bf16 v[48:51], v[214:217], v[162:165], v[48:51]
	v_mfma_f32_16x16x32_bf16 v[64:67], v[214:217], v[178:181], v[64:67]
	s_waitcnt lgkmcnt(2)
	v_mfma_f32_16x16x32_bf16 v[174:177], v[218:221], v[162:165], v[174:177]
	ds_read_b128 v[162:165], v6 offset:8192
	v_mfma_f32_16x16x32_bf16 v[170:173], v[218:221], v[178:181], v[170:173]
	ds_read_b128 v[178:181], v6 offset:10240
	s_waitcnt lgkmcnt(3)
	s_mov_b32 m0, s26
	v_mfma_f32_16x16x32_bf16 v[72:75], v[158:161], v[222:225], v[72:75]
	global_load_lds_dwordx4 v0, s[52:53]
	v_mfma_f32_16x16x32_bf16 v[76:79], v[166:169], v[222:225], v[76:79]
	v_mfma_f32_16x16x32_bf16 v[80:83], v[214:217], v[222:225], v[80:83]
	v_mfma_f32_16x16x32_bf16 v[32:35], v[218:221], v[222:225], v[32:35]
	ds_read_b128 v[222:225], v6 offset:12288
	s_waitcnt lgkmcnt(3)
	v_mfma_f32_16x16x32_bf16 v[88:91], v[158:161], v[226:229], v[88:91]
	s_mov_b32 m0, s41
	v_mfma_f32_16x16x32_bf16 v[92:95], v[166:169], v[226:229], v[92:95]
	global_load_lds_dwordx4 v2, s[50:51]
	v_mfma_f32_16x16x32_bf16 v[96:99], v[214:217], v[226:229], v[96:99]
	v_mfma_f32_16x16x32_bf16 v[36:39], v[218:221], v[226:229], v[36:39]
	ds_read_b128 v[226:229], v6 offset:14336
	s_waitcnt lgkmcnt(3)
	v_mfma_f32_16x16x32_bf16 v[104:107], v[158:161], v[162:165], v[104:107]
	s_waitcnt lgkmcnt(2)
	v_mfma_f32_16x16x32_bf16 v[116:119], v[158:161], v[178:181], v[116:119]
	s_waitcnt lgkmcnt(1)
	s_mov_b32 m0, s42
	v_mfma_f32_16x16x32_bf16 v[128:131], v[158:161], v[222:225], v[128:131]
	global_load_lds_dwordx4 v2, s[52:53]
	s_waitcnt lgkmcnt(0)
	v_mfma_f32_16x16x32_bf16 v[100:103], v[158:161], v[226:229], v[100:103]
	ds_read_b128 v[158:161], v7 offset:33792
	v_mfma_f32_16x16x32_bf16 v[108:111], v[166:169], v[162:165], v[108:111]
	v_mfma_f32_16x16x32_bf16 v[120:123], v[166:169], v[178:181], v[120:123]
	v_mfma_f32_16x16x32_bf16 v[132:135], v[166:169], v[222:225], v[132:135]
	s_mov_b32 m0, s43
	v_mfma_f32_16x16x32_bf16 v[140:143], v[166:169], v[226:229], v[140:143]
	global_load_lds_dwordx4 v4, s[50:51]
	ds_read_b128 v[166:169], v6 offset:1024
	v_mfma_f32_16x16x32_bf16 v[112:115], v[214:217], v[162:165], v[112:115]
	v_mfma_f32_16x16x32_bf16 v[52:55], v[218:221], v[162:165], v[52:55]
	ds_read_b128 v[162:165], v7 offset:35840
	v_mfma_f32_16x16x32_bf16 v[124:127], v[214:217], v[178:181], v[124:127]
	v_mfma_f32_16x16x32_bf16 v[68:71], v[218:221], v[178:181], v[68:71]
	ds_read_b128 v[178:181], v6 offset:3072
	s_mov_b32 m0, s44
	v_mfma_f32_16x16x32_bf16 v[136:139], v[214:217], v[222:225], v[136:139]
	global_load_lds_dwordx4 v4, s[52:53]
	v_mfma_f32_16x16x32_bf16 v[84:87], v[218:221], v[222:225], v[84:87]
	ds_read_b128 v[222:225], v6 offset:5120
	v_mfma_f32_16x16x32_bf16 v[150:153], v[214:217], v[226:229], v[150:153]
	ds_read_b128 v[214:217], v7 offset:37888
	v_mfma_f32_16x16x32_bf16 v[154:157], v[218:221], v[226:229], v[154:157]
	ds_read_b128 v[218:221], v7 offset:39936
	ds_read_b128 v[226:229], v6 offset:7168
	s_waitcnt lgkmcnt(6)
	v_mfma_f32_16x16x32_bf16 v[40:43], v[158:161], v[166:169], v[40:43]
	s_waitcnt lgkmcnt(5)
	s_mov_b32 m0, s45
	v_mfma_f32_16x16x32_bf16 v[44:47], v[162:165], v[166:169], v[44:47]
	global_load_lds_dwordx4 v146, s[50:51]
	s_waitcnt lgkmcnt(4)
	v_mfma_f32_16x16x32_bf16 v[56:59], v[158:161], v[178:181], v[56:59]
	v_mfma_f32_16x16x32_bf16 v[60:63], v[162:165], v[178:181], v[60:63]
	s_waitcnt lgkmcnt(3)
	v_mfma_f32_16x16x32_bf16 v[72:75], v[158:161], v[222:225], v[72:75]
	v_mfma_f32_16x16x32_bf16 v[76:79], v[162:165], v[222:225], v[76:79]
	s_waitcnt lgkmcnt(2)
	s_mov_b32 m0, s46
	v_mfma_f32_16x16x32_bf16 v[48:51], v[214:217], v[166:169], v[48:51]
	global_load_lds_dwordx4 v146, s[52:53]
	s_waitcnt lgkmcnt(1)
	v_mfma_f32_16x16x32_bf16 v[174:177], v[218:221], v[166:169], v[174:177]
	ds_read_b128 v[166:169], v6 offset:9216
	v_mfma_f32_16x16x32_bf16 v[64:67], v[214:217], v[178:181], v[64:67]
	v_mfma_f32_16x16x32_bf16 v[170:173], v[218:221], v[178:181], v[170:173]
	ds_read_b128 v[178:181], v6 offset:11264
	v_mfma_f32_16x16x32_bf16 v[80:83], v[214:217], v[222:225], v[80:83]
	v_mfma_f32_16x16x32_bf16 v[32:35], v[218:221], v[222:225], v[32:35]
	ds_read_b128 v[222:225], v6 offset:13312
	s_waitcnt lgkmcnt(3)
	v_mfma_f32_16x16x32_bf16 v[88:91], v[158:161], v[226:229], v[88:91]
	v_mfma_f32_16x16x32_bf16 v[92:95], v[162:165], v[226:229], v[92:95]
	v_mfma_f32_16x16x32_bf16 v[96:99], v[214:217], v[226:229], v[96:99]
	v_mfma_f32_16x16x32_bf16 v[36:39], v[218:221], v[226:229], v[36:39]
	ds_read_b128 v[226:229], v6 offset:15360
	s_waitcnt lgkmcnt(3)
	v_mfma_f32_16x16x32_bf16 v[104:107], v[158:161], v[166:169], v[104:107]
	v_mfma_f32_16x16x32_bf16 v[108:111], v[162:165], v[166:169], v[108:111]
	v_mfma_f32_16x16x32_bf16 v[112:115], v[214:217], v[166:169], v[112:115]
	v_mfma_f32_16x16x32_bf16 v[52:55], v[218:221], v[166:169], v[52:55]
	s_waitcnt lgkmcnt(2)
	v_mfma_f32_16x16x32_bf16 v[116:119], v[158:161], v[178:181], v[116:119]
	v_mfma_f32_16x16x32_bf16 v[120:123], v[162:165], v[178:181], v[120:123]
	v_mfma_f32_16x16x32_bf16 v[124:127], v[214:217], v[178:181], v[124:127]
	v_mfma_f32_16x16x32_bf16 v[68:71], v[218:221], v[178:181], v[68:71]
	s_waitcnt lgkmcnt(1)
	v_mfma_f32_16x16x32_bf16 v[128:131], v[158:161], v[222:225], v[128:131]
	v_mfma_f32_16x16x32_bf16 v[132:135], v[162:165], v[222:225], v[132:135]
	v_mfma_f32_16x16x32_bf16 v[136:139], v[214:217], v[222:225], v[136:139]
	v_mfma_f32_16x16x32_bf16 v[84:87], v[218:221], v[222:225], v[84:87]
	s_waitcnt lgkmcnt(0)
	v_mfma_f32_16x16x32_bf16 v[100:103], v[158:161], v[226:229], v[100:103]
	v_mfma_f32_16x16x32_bf16 v[140:143], v[162:165], v[226:229], v[140:143]
	v_mfma_f32_16x16x32_bf16 v[150:153], v[214:217], v[226:229], v[150:153]
	v_mfma_f32_16x16x32_bf16 v[154:157], v[218:221], v[226:229], v[154:157]
	s_add_u32 s50, s14, 0xd00
	s_addc_u32 s51, s15, 0
	s_add_u32 s52, s20, 0xd00
	s_waitcnt vmcnt(0)
	s_barrier
	s_addc_u32 s53, s21, 0
	ds_read_b128 v[158:161], v8
	ds_read_b128 v[162:165], v12
	ds_read_b128 v[166:169], v9
	ds_read_b128 v[178:181], v13
	ds_read_b128 v[214:217], v11
	ds_read_b128 v[218:221], v10
	ds_read_b128 v[222:225], v14
	ds_read_b128 v[226:229], v15
	s_waitcnt lgkmcnt(6)
	v_mfma_f32_16x16x32_bf16 v[40:43], v[158:161], v[162:165], v[40:43]
	s_waitcnt lgkmcnt(5)
	v_mfma_f32_16x16x32_bf16 v[44:47], v[166:169], v[162:165], v[44:47]
	s_waitcnt lgkmcnt(4)
	v_mfma_f32_16x16x32_bf16 v[56:59], v[158:161], v[178:181], v[56:59]
	s_mov_b32 m0, s1
	v_mfma_f32_16x16x32_bf16 v[60:63], v[166:169], v[178:181], v[60:63]
	global_load_lds_dwordx4 v0, s[50:51]
	s_waitcnt lgkmcnt(3)
	v_mfma_f32_16x16x32_bf16 v[48:51], v[214:217], v[162:165], v[48:51]
	v_mfma_f32_16x16x32_bf16 v[64:67], v[214:217], v[178:181], v[64:67]
	s_waitcnt lgkmcnt(2)
	v_mfma_f32_16x16x32_bf16 v[174:177], v[218:221], v[162:165], v[174:177]
	ds_read_b128 v[162:165], v16
	v_mfma_f32_16x16x32_bf16 v[170:173], v[218:221], v[178:181], v[170:173]
	ds_read_b128 v[178:181], v17
	s_waitcnt lgkmcnt(3)
	s_mov_b32 m0, s34
	v_mfma_f32_16x16x32_bf16 v[72:75], v[158:161], v[222:225], v[72:75]
	global_load_lds_dwordx4 v0, s[52:53]
	v_mfma_f32_16x16x32_bf16 v[76:79], v[166:169], v[222:225], v[76:79]
	v_mfma_f32_16x16x32_bf16 v[80:83], v[214:217], v[222:225], v[80:83]
	v_mfma_f32_16x16x32_bf16 v[32:35], v[218:221], v[222:225], v[32:35]
	ds_read_b128 v[222:225], v18
	s_waitcnt lgkmcnt(3)
	v_mfma_f32_16x16x32_bf16 v[88:91], v[158:161], v[226:229], v[88:91]
	s_mov_b32 m0, s35
	v_mfma_f32_16x16x32_bf16 v[92:95], v[166:169], v[226:229], v[92:95]
	global_load_lds_dwordx4 v2, s[50:51]
	v_mfma_f32_16x16x32_bf16 v[96:99], v[214:217], v[226:229], v[96:99]
	v_mfma_f32_16x16x32_bf16 v[36:39], v[218:221], v[226:229], v[36:39]
	ds_read_b128 v[226:229], v19
	s_waitcnt lgkmcnt(3)
	v_mfma_f32_16x16x32_bf16 v[104:107], v[158:161], v[162:165], v[104:107]
	s_waitcnt lgkmcnt(2)
	v_mfma_f32_16x16x32_bf16 v[116:119], v[158:161], v[178:181], v[116:119]
	s_waitcnt lgkmcnt(1)
	s_mov_b32 m0, s36
	v_mfma_f32_16x16x32_bf16 v[128:131], v[158:161], v[222:225], v[128:131]
	global_load_lds_dwordx4 v2, s[52:53]
	s_waitcnt lgkmcnt(0)
	v_mfma_f32_16x16x32_bf16 v[100:103], v[158:161], v[226:229], v[100:103]
	ds_read_b128 v[158:161], v20
	v_mfma_f32_16x16x32_bf16 v[108:111], v[166:169], v[162:165], v[108:111]
	v_mfma_f32_16x16x32_bf16 v[120:123], v[166:169], v[178:181], v[120:123]
	v_mfma_f32_16x16x32_bf16 v[132:135], v[166:169], v[222:225], v[132:135]
	s_mov_b32 m0, s37
	v_mfma_f32_16x16x32_bf16 v[140:143], v[166:169], v[226:229], v[140:143]
	global_load_lds_dwordx4 v4, s[50:51]
	ds_read_b128 v[166:169], v24
	v_mfma_f32_16x16x32_bf16 v[112:115], v[214:217], v[162:165], v[112:115]
	v_mfma_f32_16x16x32_bf16 v[52:55], v[218:221], v[162:165], v[52:55]
	ds_read_b128 v[162:165], v21
	v_mfma_f32_16x16x32_bf16 v[124:127], v[214:217], v[178:181], v[124:127]
	v_mfma_f32_16x16x32_bf16 v[68:71], v[218:221], v[178:181], v[68:71]
	ds_read_b128 v[178:181], v25
	s_mov_b32 m0, s38
	v_mfma_f32_16x16x32_bf16 v[136:139], v[214:217], v[222:225], v[136:139]
	global_load_lds_dwordx4 v4, s[52:53]
	v_mfma_f32_16x16x32_bf16 v[84:87], v[218:221], v[222:225], v[84:87]
	ds_read_b128 v[222:225], v26
	v_mfma_f32_16x16x32_bf16 v[150:153], v[214:217], v[226:229], v[150:153]
	ds_read_b128 v[214:217], v23
	v_mfma_f32_16x16x32_bf16 v[154:157], v[218:221], v[226:229], v[154:157]
	ds_read_b128 v[218:221], v22
	ds_read_b128 v[226:229], v27
	s_waitcnt lgkmcnt(6)
	v_mfma_f32_16x16x32_bf16 v[40:43], v[158:161], v[166:169], v[40:43]
	s_waitcnt lgkmcnt(5)
	s_mov_b32 m0, s39
	v_mfma_f32_16x16x32_bf16 v[44:47], v[162:165], v[166:169], v[44:47]
	global_load_lds_dwordx4 v146, s[50:51]
	s_waitcnt lgkmcnt(4)
	v_mfma_f32_16x16x32_bf16 v[56:59], v[158:161], v[178:181], v[56:59]
	v_mfma_f32_16x16x32_bf16 v[60:63], v[162:165], v[178:181], v[60:63]
	s_waitcnt lgkmcnt(3)
	v_mfma_f32_16x16x32_bf16 v[72:75], v[158:161], v[222:225], v[72:75]
	v_mfma_f32_16x16x32_bf16 v[76:79], v[162:165], v[222:225], v[76:79]
	s_waitcnt lgkmcnt(2)
	s_mov_b32 m0, s40
	v_mfma_f32_16x16x32_bf16 v[48:51], v[214:217], v[166:169], v[48:51]
	global_load_lds_dwordx4 v146, s[52:53]
	s_waitcnt lgkmcnt(1)
	v_mfma_f32_16x16x32_bf16 v[174:177], v[218:221], v[166:169], v[174:177]
	ds_read_b128 v[166:169], v28
	v_mfma_f32_16x16x32_bf16 v[64:67], v[214:217], v[178:181], v[64:67]
	v_mfma_f32_16x16x32_bf16 v[170:173], v[218:221], v[178:181], v[170:173]
	ds_read_b128 v[178:181], v29
	v_mfma_f32_16x16x32_bf16 v[80:83], v[214:217], v[222:225], v[80:83]
	v_mfma_f32_16x16x32_bf16 v[32:35], v[218:221], v[222:225], v[32:35]
	ds_read_b128 v[222:225], v30
	s_waitcnt lgkmcnt(3)
	v_mfma_f32_16x16x32_bf16 v[88:91], v[158:161], v[226:229], v[88:91]
	v_mfma_f32_16x16x32_bf16 v[92:95], v[162:165], v[226:229], v[92:95]
	v_mfma_f32_16x16x32_bf16 v[96:99], v[214:217], v[226:229], v[96:99]
	v_mfma_f32_16x16x32_bf16 v[36:39], v[218:221], v[226:229], v[36:39]
	ds_read_b128 v[226:229], v31
	s_waitcnt lgkmcnt(3)
	v_mfma_f32_16x16x32_bf16 v[104:107], v[158:161], v[166:169], v[104:107]
	v_mfma_f32_16x16x32_bf16 v[108:111], v[162:165], v[166:169], v[108:111]
	v_mfma_f32_16x16x32_bf16 v[112:115], v[214:217], v[166:169], v[112:115]
	v_mfma_f32_16x16x32_bf16 v[52:55], v[218:221], v[166:169], v[52:55]
	s_waitcnt lgkmcnt(2)
	v_mfma_f32_16x16x32_bf16 v[116:119], v[158:161], v[178:181], v[116:119]
	v_mfma_f32_16x16x32_bf16 v[120:123], v[162:165], v[178:181], v[120:123]
	v_mfma_f32_16x16x32_bf16 v[124:127], v[214:217], v[178:181], v[124:127]
	v_mfma_f32_16x16x32_bf16 v[68:71], v[218:221], v[178:181], v[68:71]
	s_waitcnt lgkmcnt(1)
	v_mfma_f32_16x16x32_bf16 v[128:131], v[158:161], v[222:225], v[128:131]
	v_mfma_f32_16x16x32_bf16 v[132:135], v[162:165], v[222:225], v[132:135]
	v_mfma_f32_16x16x32_bf16 v[136:139], v[214:217], v[222:225], v[136:139]
	v_mfma_f32_16x16x32_bf16 v[84:87], v[218:221], v[222:225], v[84:87]
	s_waitcnt lgkmcnt(0)
	v_mfma_f32_16x16x32_bf16 v[100:103], v[158:161], v[226:229], v[100:103]
	v_mfma_f32_16x16x32_bf16 v[140:143], v[162:165], v[226:229], v[140:143]
	v_mfma_f32_16x16x32_bf16 v[150:153], v[214:217], v[226:229], v[150:153]
	v_mfma_f32_16x16x32_bf16 v[154:157], v[218:221], v[226:229], v[154:157]
	s_add_u32 s50, s14, 0xd80
	s_addc_u32 s51, s15, 0
	s_add_u32 s52, s20, 0xd80
	s_waitcnt vmcnt(0)
	s_barrier
	s_addc_u32 s53, s21, 0
	ds_read_b128 v[158:161], v7 offset:32768
	ds_read_b128 v[162:165], v6
	ds_read_b128 v[166:169], v7 offset:34816
	ds_read_b128 v[178:181], v6 offset:2048
	ds_read_b128 v[214:217], v7 offset:36864
	ds_read_b128 v[218:221], v7 offset:38912
	ds_read_b128 v[222:225], v6 offset:4096
	ds_read_b128 v[226:229], v6 offset:6144
	s_waitcnt lgkmcnt(6)
	v_mfma_f32_16x16x32_bf16 v[40:43], v[158:161], v[162:165], v[40:43]
	s_waitcnt lgkmcnt(5)
	v_mfma_f32_16x16x32_bf16 v[44:47], v[166:169], v[162:165], v[44:47]
	s_waitcnt lgkmcnt(4)
	v_mfma_f32_16x16x32_bf16 v[56:59], v[158:161], v[178:181], v[56:59]
	s_mov_b32 m0, s27
	v_mfma_f32_16x16x32_bf16 v[60:63], v[166:169], v[178:181], v[60:63]
	global_load_lds_dwordx4 v0, s[50:51]
	s_waitcnt lgkmcnt(3)
	v_mfma_f32_16x16x32_bf16 v[48:51], v[214:217], v[162:165], v[48:51]
	v_mfma_f32_16x16x32_bf16 v[64:67], v[214:217], v[178:181], v[64:67]
	s_waitcnt lgkmcnt(2)
	v_mfma_f32_16x16x32_bf16 v[174:177], v[218:221], v[162:165], v[174:177]
	ds_read_b128 v[162:165], v6 offset:8192
	v_mfma_f32_16x16x32_bf16 v[170:173], v[218:221], v[178:181], v[170:173]
	ds_read_b128 v[178:181], v6 offset:10240
	s_waitcnt lgkmcnt(3)
	s_mov_b32 m0, s26
	v_mfma_f32_16x16x32_bf16 v[72:75], v[158:161], v[222:225], v[72:75]
	global_load_lds_dwordx4 v0, s[52:53]
	v_mfma_f32_16x16x32_bf16 v[76:79], v[166:169], v[222:225], v[76:79]
	v_mfma_f32_16x16x32_bf16 v[80:83], v[214:217], v[222:225], v[80:83]
	v_mfma_f32_16x16x32_bf16 v[32:35], v[218:221], v[222:225], v[32:35]
	ds_read_b128 v[222:225], v6 offset:12288
	s_waitcnt lgkmcnt(3)
	v_mfma_f32_16x16x32_bf16 v[88:91], v[158:161], v[226:229], v[88:91]
	s_mov_b32 m0, s41
	v_mfma_f32_16x16x32_bf16 v[92:95], v[166:169], v[226:229], v[92:95]
	global_load_lds_dwordx4 v2, s[50:51]
	v_mfma_f32_16x16x32_bf16 v[96:99], v[214:217], v[226:229], v[96:99]
	v_mfma_f32_16x16x32_bf16 v[36:39], v[218:221], v[226:229], v[36:39]
	ds_read_b128 v[226:229], v6 offset:14336
	s_waitcnt lgkmcnt(3)
	v_mfma_f32_16x16x32_bf16 v[104:107], v[158:161], v[162:165], v[104:107]
	s_waitcnt lgkmcnt(2)
	v_mfma_f32_16x16x32_bf16 v[116:119], v[158:161], v[178:181], v[116:119]
	s_waitcnt lgkmcnt(1)
	s_mov_b32 m0, s42
	v_mfma_f32_16x16x32_bf16 v[128:131], v[158:161], v[222:225], v[128:131]
	global_load_lds_dwordx4 v2, s[52:53]
	s_waitcnt lgkmcnt(0)
	v_mfma_f32_16x16x32_bf16 v[100:103], v[158:161], v[226:229], v[100:103]
	ds_read_b128 v[158:161], v7 offset:33792
	v_mfma_f32_16x16x32_bf16 v[108:111], v[166:169], v[162:165], v[108:111]
	v_mfma_f32_16x16x32_bf16 v[120:123], v[166:169], v[178:181], v[120:123]
	v_mfma_f32_16x16x32_bf16 v[132:135], v[166:169], v[222:225], v[132:135]
	s_mov_b32 m0, s43
	v_mfma_f32_16x16x32_bf16 v[140:143], v[166:169], v[226:229], v[140:143]
	global_load_lds_dwordx4 v4, s[50:51]
	ds_read_b128 v[166:169], v6 offset:1024
	v_mfma_f32_16x16x32_bf16 v[112:115], v[214:217], v[162:165], v[112:115]
	v_mfma_f32_16x16x32_bf16 v[52:55], v[218:221], v[162:165], v[52:55]
	ds_read_b128 v[162:165], v7 offset:35840
	v_mfma_f32_16x16x32_bf16 v[124:127], v[214:217], v[178:181], v[124:127]
	v_mfma_f32_16x16x32_bf16 v[68:71], v[218:221], v[178:181], v[68:71]
	ds_read_b128 v[178:181], v6 offset:3072
	s_mov_b32 m0, s44
	v_mfma_f32_16x16x32_bf16 v[136:139], v[214:217], v[222:225], v[136:139]
	global_load_lds_dwordx4 v4, s[52:53]
	v_mfma_f32_16x16x32_bf16 v[84:87], v[218:221], v[222:225], v[84:87]
	ds_read_b128 v[222:225], v6 offset:5120
	v_mfma_f32_16x16x32_bf16 v[150:153], v[214:217], v[226:229], v[150:153]
	ds_read_b128 v[214:217], v7 offset:37888
	v_mfma_f32_16x16x32_bf16 v[154:157], v[218:221], v[226:229], v[154:157]
	ds_read_b128 v[218:221], v7 offset:39936
	ds_read_b128 v[226:229], v6 offset:7168
	s_waitcnt lgkmcnt(6)
	v_mfma_f32_16x16x32_bf16 v[40:43], v[158:161], v[166:169], v[40:43]
	s_waitcnt lgkmcnt(5)
	s_mov_b32 m0, s45
	v_mfma_f32_16x16x32_bf16 v[44:47], v[162:165], v[166:169], v[44:47]
	global_load_lds_dwordx4 v146, s[50:51]
	s_waitcnt lgkmcnt(4)
	v_mfma_f32_16x16x32_bf16 v[56:59], v[158:161], v[178:181], v[56:59]
	v_mfma_f32_16x16x32_bf16 v[60:63], v[162:165], v[178:181], v[60:63]
	s_waitcnt lgkmcnt(3)
	v_mfma_f32_16x16x32_bf16 v[72:75], v[158:161], v[222:225], v[72:75]
	v_mfma_f32_16x16x32_bf16 v[76:79], v[162:165], v[222:225], v[76:79]
	s_waitcnt lgkmcnt(2)
	s_mov_b32 m0, s46
	v_mfma_f32_16x16x32_bf16 v[48:51], v[214:217], v[166:169], v[48:51]
	global_load_lds_dwordx4 v146, s[52:53]
	s_waitcnt lgkmcnt(1)
	v_mfma_f32_16x16x32_bf16 v[174:177], v[218:221], v[166:169], v[174:177]
	ds_read_b128 v[166:169], v6 offset:9216
	v_mfma_f32_16x16x32_bf16 v[64:67], v[214:217], v[178:181], v[64:67]
	v_mfma_f32_16x16x32_bf16 v[170:173], v[218:221], v[178:181], v[170:173]
	ds_read_b128 v[178:181], v6 offset:11264
	v_mfma_f32_16x16x32_bf16 v[80:83], v[214:217], v[222:225], v[80:83]
	v_mfma_f32_16x16x32_bf16 v[32:35], v[218:221], v[222:225], v[32:35]
	ds_read_b128 v[222:225], v6 offset:13312
	s_waitcnt lgkmcnt(3)
	v_mfma_f32_16x16x32_bf16 v[88:91], v[158:161], v[226:229], v[88:91]
	v_mfma_f32_16x16x32_bf16 v[92:95], v[162:165], v[226:229], v[92:95]
	v_mfma_f32_16x16x32_bf16 v[96:99], v[214:217], v[226:229], v[96:99]
	v_mfma_f32_16x16x32_bf16 v[36:39], v[218:221], v[226:229], v[36:39]
	ds_read_b128 v[226:229], v6 offset:15360
	s_waitcnt lgkmcnt(3)
	v_mfma_f32_16x16x32_bf16 v[104:107], v[158:161], v[166:169], v[104:107]
	v_mfma_f32_16x16x32_bf16 v[108:111], v[162:165], v[166:169], v[108:111]
	v_mfma_f32_16x16x32_bf16 v[112:115], v[214:217], v[166:169], v[112:115]
	v_mfma_f32_16x16x32_bf16 v[52:55], v[218:221], v[166:169], v[52:55]
	s_waitcnt lgkmcnt(2)
	v_mfma_f32_16x16x32_bf16 v[116:119], v[158:161], v[178:181], v[116:119]
	v_mfma_f32_16x16x32_bf16 v[120:123], v[162:165], v[178:181], v[120:123]
	v_mfma_f32_16x16x32_bf16 v[124:127], v[214:217], v[178:181], v[124:127]
	v_mfma_f32_16x16x32_bf16 v[68:71], v[218:221], v[178:181], v[68:71]
	s_waitcnt lgkmcnt(1)
	v_mfma_f32_16x16x32_bf16 v[128:131], v[158:161], v[222:225], v[128:131]
	v_mfma_f32_16x16x32_bf16 v[132:135], v[162:165], v[222:225], v[132:135]
	v_mfma_f32_16x16x32_bf16 v[136:139], v[214:217], v[222:225], v[136:139]
	v_mfma_f32_16x16x32_bf16 v[84:87], v[218:221], v[222:225], v[84:87]
	s_waitcnt lgkmcnt(0)
	v_mfma_f32_16x16x32_bf16 v[100:103], v[158:161], v[226:229], v[100:103]
	v_mfma_f32_16x16x32_bf16 v[140:143], v[162:165], v[226:229], v[140:143]
	v_mfma_f32_16x16x32_bf16 v[150:153], v[214:217], v[226:229], v[150:153]
	v_mfma_f32_16x16x32_bf16 v[154:157], v[218:221], v[226:229], v[154:157]
	s_add_u32 s50, s14, 0xe00
	s_addc_u32 s51, s15, 0
	s_add_u32 s52, s20, 0xe00
	s_waitcnt vmcnt(0)
	s_barrier
	s_addc_u32 s53, s21, 0
	ds_read_b128 v[158:161], v8
	ds_read_b128 v[162:165], v12
	ds_read_b128 v[166:169], v9
	ds_read_b128 v[178:181], v13
	ds_read_b128 v[214:217], v11
	ds_read_b128 v[218:221], v10
	ds_read_b128 v[222:225], v14
	ds_read_b128 v[226:229], v15
	s_waitcnt lgkmcnt(6)
	v_mfma_f32_16x16x32_bf16 v[40:43], v[158:161], v[162:165], v[40:43]
	s_waitcnt lgkmcnt(5)
	v_mfma_f32_16x16x32_bf16 v[44:47], v[166:169], v[162:165], v[44:47]
	s_waitcnt lgkmcnt(4)
	v_mfma_f32_16x16x32_bf16 v[56:59], v[158:161], v[178:181], v[56:59]
	s_mov_b32 m0, s1
	v_mfma_f32_16x16x32_bf16 v[60:63], v[166:169], v[178:181], v[60:63]
	global_load_lds_dwordx4 v0, s[50:51]
	s_waitcnt lgkmcnt(3)
	v_mfma_f32_16x16x32_bf16 v[48:51], v[214:217], v[162:165], v[48:51]
	v_mfma_f32_16x16x32_bf16 v[64:67], v[214:217], v[178:181], v[64:67]
	s_waitcnt lgkmcnt(2)
	v_mfma_f32_16x16x32_bf16 v[174:177], v[218:221], v[162:165], v[174:177]
	ds_read_b128 v[162:165], v16
	v_mfma_f32_16x16x32_bf16 v[170:173], v[218:221], v[178:181], v[170:173]
	ds_read_b128 v[178:181], v17
	s_waitcnt lgkmcnt(3)
	s_mov_b32 m0, s34
	v_mfma_f32_16x16x32_bf16 v[72:75], v[158:161], v[222:225], v[72:75]
	global_load_lds_dwordx4 v0, s[52:53]
	v_mfma_f32_16x16x32_bf16 v[76:79], v[166:169], v[222:225], v[76:79]
	v_mfma_f32_16x16x32_bf16 v[80:83], v[214:217], v[222:225], v[80:83]
	v_mfma_f32_16x16x32_bf16 v[32:35], v[218:221], v[222:225], v[32:35]
	ds_read_b128 v[222:225], v18
	s_waitcnt lgkmcnt(3)
	v_mfma_f32_16x16x32_bf16 v[88:91], v[158:161], v[226:229], v[88:91]
	s_mov_b32 m0, s35
	v_mfma_f32_16x16x32_bf16 v[92:95], v[166:169], v[226:229], v[92:95]
	global_load_lds_dwordx4 v2, s[50:51]
	v_mfma_f32_16x16x32_bf16 v[96:99], v[214:217], v[226:229], v[96:99]
	v_mfma_f32_16x16x32_bf16 v[36:39], v[218:221], v[226:229], v[36:39]
	ds_read_b128 v[226:229], v19
	s_waitcnt lgkmcnt(3)
	v_mfma_f32_16x16x32_bf16 v[104:107], v[158:161], v[162:165], v[104:107]
	s_waitcnt lgkmcnt(2)
	v_mfma_f32_16x16x32_bf16 v[116:119], v[158:161], v[178:181], v[116:119]
	s_waitcnt lgkmcnt(1)
	s_mov_b32 m0, s36
	v_mfma_f32_16x16x32_bf16 v[128:131], v[158:161], v[222:225], v[128:131]
	global_load_lds_dwordx4 v2, s[52:53]
	s_waitcnt lgkmcnt(0)
	v_mfma_f32_16x16x32_bf16 v[100:103], v[158:161], v[226:229], v[100:103]
	ds_read_b128 v[158:161], v20
	v_mfma_f32_16x16x32_bf16 v[108:111], v[166:169], v[162:165], v[108:111]
	v_mfma_f32_16x16x32_bf16 v[120:123], v[166:169], v[178:181], v[120:123]
	v_mfma_f32_16x16x32_bf16 v[132:135], v[166:169], v[222:225], v[132:135]
	s_mov_b32 m0, s37
	v_mfma_f32_16x16x32_bf16 v[140:143], v[166:169], v[226:229], v[140:143]
	global_load_lds_dwordx4 v4, s[50:51]
	ds_read_b128 v[166:169], v24
	v_mfma_f32_16x16x32_bf16 v[112:115], v[214:217], v[162:165], v[112:115]
	v_mfma_f32_16x16x32_bf16 v[52:55], v[218:221], v[162:165], v[52:55]
	ds_read_b128 v[162:165], v21
	v_mfma_f32_16x16x32_bf16 v[124:127], v[214:217], v[178:181], v[124:127]
	v_mfma_f32_16x16x32_bf16 v[68:71], v[218:221], v[178:181], v[68:71]
	ds_read_b128 v[178:181], v25
	s_mov_b32 m0, s38
	v_mfma_f32_16x16x32_bf16 v[136:139], v[214:217], v[222:225], v[136:139]
	global_load_lds_dwordx4 v4, s[52:53]
	v_mfma_f32_16x16x32_bf16 v[84:87], v[218:221], v[222:225], v[84:87]
	ds_read_b128 v[222:225], v26
	v_mfma_f32_16x16x32_bf16 v[150:153], v[214:217], v[226:229], v[150:153]
	ds_read_b128 v[214:217], v23
	v_mfma_f32_16x16x32_bf16 v[154:157], v[218:221], v[226:229], v[154:157]
	ds_read_b128 v[218:221], v22
	ds_read_b128 v[226:229], v27
	s_waitcnt lgkmcnt(6)
	v_mfma_f32_16x16x32_bf16 v[40:43], v[158:161], v[166:169], v[40:43]
	s_waitcnt lgkmcnt(5)
	s_mov_b32 m0, s39
	v_mfma_f32_16x16x32_bf16 v[44:47], v[162:165], v[166:169], v[44:47]
	global_load_lds_dwordx4 v146, s[50:51]
	s_waitcnt lgkmcnt(4)
	v_mfma_f32_16x16x32_bf16 v[56:59], v[158:161], v[178:181], v[56:59]
	v_mfma_f32_16x16x32_bf16 v[60:63], v[162:165], v[178:181], v[60:63]
	s_waitcnt lgkmcnt(3)
	v_mfma_f32_16x16x32_bf16 v[72:75], v[158:161], v[222:225], v[72:75]
	v_mfma_f32_16x16x32_bf16 v[76:79], v[162:165], v[222:225], v[76:79]
	s_waitcnt lgkmcnt(2)
	s_mov_b32 m0, s40
	v_mfma_f32_16x16x32_bf16 v[48:51], v[214:217], v[166:169], v[48:51]
	global_load_lds_dwordx4 v146, s[52:53]
	s_waitcnt lgkmcnt(1)
	v_mfma_f32_16x16x32_bf16 v[174:177], v[218:221], v[166:169], v[174:177]
	ds_read_b128 v[166:169], v28
	v_mfma_f32_16x16x32_bf16 v[64:67], v[214:217], v[178:181], v[64:67]
	v_mfma_f32_16x16x32_bf16 v[170:173], v[218:221], v[178:181], v[170:173]
	ds_read_b128 v[178:181], v29
	v_mfma_f32_16x16x32_bf16 v[80:83], v[214:217], v[222:225], v[80:83]
	v_mfma_f32_16x16x32_bf16 v[32:35], v[218:221], v[222:225], v[32:35]
	ds_read_b128 v[222:225], v30
	s_waitcnt lgkmcnt(3)
	v_mfma_f32_16x16x32_bf16 v[88:91], v[158:161], v[226:229], v[88:91]
	v_mfma_f32_16x16x32_bf16 v[92:95], v[162:165], v[226:229], v[92:95]
	v_mfma_f32_16x16x32_bf16 v[96:99], v[214:217], v[226:229], v[96:99]
	v_mfma_f32_16x16x32_bf16 v[36:39], v[218:221], v[226:229], v[36:39]
	ds_read_b128 v[226:229], v31
	s_waitcnt lgkmcnt(3)
	v_mfma_f32_16x16x32_bf16 v[104:107], v[158:161], v[166:169], v[104:107]
	v_mfma_f32_16x16x32_bf16 v[108:111], v[162:165], v[166:169], v[108:111]
	v_mfma_f32_16x16x32_bf16 v[112:115], v[214:217], v[166:169], v[112:115]
	v_mfma_f32_16x16x32_bf16 v[52:55], v[218:221], v[166:169], v[52:55]
	s_waitcnt lgkmcnt(2)
	v_mfma_f32_16x16x32_bf16 v[116:119], v[158:161], v[178:181], v[116:119]
	v_mfma_f32_16x16x32_bf16 v[120:123], v[162:165], v[178:181], v[120:123]
	v_mfma_f32_16x16x32_bf16 v[124:127], v[214:217], v[178:181], v[124:127]
	v_mfma_f32_16x16x32_bf16 v[68:71], v[218:221], v[178:181], v[68:71]
	s_waitcnt lgkmcnt(1)
	v_mfma_f32_16x16x32_bf16 v[128:131], v[158:161], v[222:225], v[128:131]
	v_mfma_f32_16x16x32_bf16 v[132:135], v[162:165], v[222:225], v[132:135]
	v_mfma_f32_16x16x32_bf16 v[136:139], v[214:217], v[222:225], v[136:139]
	v_mfma_f32_16x16x32_bf16 v[84:87], v[218:221], v[222:225], v[84:87]
	s_waitcnt lgkmcnt(0)
	v_mfma_f32_16x16x32_bf16 v[100:103], v[158:161], v[226:229], v[100:103]
	v_mfma_f32_16x16x32_bf16 v[140:143], v[162:165], v[226:229], v[140:143]
	v_mfma_f32_16x16x32_bf16 v[150:153], v[214:217], v[226:229], v[150:153]
	v_mfma_f32_16x16x32_bf16 v[154:157], v[218:221], v[226:229], v[154:157]
	s_add_u32 s50, s14, 0xe80
	s_addc_u32 s51, s15, 0
	s_add_u32 s52, s20, 0xe80
	s_waitcnt vmcnt(0)
	s_barrier
	s_addc_u32 s53, s21, 0
	ds_read_b128 v[158:161], v7 offset:32768
	ds_read_b128 v[162:165], v6
	ds_read_b128 v[166:169], v7 offset:34816
	ds_read_b128 v[178:181], v6 offset:2048
	ds_read_b128 v[214:217], v7 offset:36864
	ds_read_b128 v[218:221], v7 offset:38912
	ds_read_b128 v[222:225], v6 offset:4096
	ds_read_b128 v[226:229], v6 offset:6144
	s_waitcnt lgkmcnt(6)
	v_mfma_f32_16x16x32_bf16 v[40:43], v[158:161], v[162:165], v[40:43]
	s_waitcnt lgkmcnt(5)
	v_mfma_f32_16x16x32_bf16 v[44:47], v[166:169], v[162:165], v[44:47]
	s_waitcnt lgkmcnt(4)
	v_mfma_f32_16x16x32_bf16 v[56:59], v[158:161], v[178:181], v[56:59]
	s_mov_b32 m0, s27
	v_mfma_f32_16x16x32_bf16 v[60:63], v[166:169], v[178:181], v[60:63]
	global_load_lds_dwordx4 v0, s[50:51]
	s_waitcnt lgkmcnt(3)
	v_mfma_f32_16x16x32_bf16 v[48:51], v[214:217], v[162:165], v[48:51]
	v_mfma_f32_16x16x32_bf16 v[64:67], v[214:217], v[178:181], v[64:67]
	s_waitcnt lgkmcnt(2)
	v_mfma_f32_16x16x32_bf16 v[174:177], v[218:221], v[162:165], v[174:177]
	ds_read_b128 v[162:165], v6 offset:8192
	v_mfma_f32_16x16x32_bf16 v[170:173], v[218:221], v[178:181], v[170:173]
	ds_read_b128 v[178:181], v6 offset:10240
	s_waitcnt lgkmcnt(3)
	s_mov_b32 m0, s26
	v_mfma_f32_16x16x32_bf16 v[72:75], v[158:161], v[222:225], v[72:75]
	global_load_lds_dwordx4 v0, s[52:53]
	v_mfma_f32_16x16x32_bf16 v[76:79], v[166:169], v[222:225], v[76:79]
	v_mfma_f32_16x16x32_bf16 v[80:83], v[214:217], v[222:225], v[80:83]
	v_mfma_f32_16x16x32_bf16 v[32:35], v[218:221], v[222:225], v[32:35]
	ds_read_b128 v[222:225], v6 offset:12288
	s_waitcnt lgkmcnt(3)
	v_mfma_f32_16x16x32_bf16 v[88:91], v[158:161], v[226:229], v[88:91]
	s_mov_b32 m0, s41
	v_mfma_f32_16x16x32_bf16 v[92:95], v[166:169], v[226:229], v[92:95]
	global_load_lds_dwordx4 v2, s[50:51]
	v_mfma_f32_16x16x32_bf16 v[96:99], v[214:217], v[226:229], v[96:99]
	v_mfma_f32_16x16x32_bf16 v[36:39], v[218:221], v[226:229], v[36:39]
	ds_read_b128 v[226:229], v6 offset:14336
	s_waitcnt lgkmcnt(3)
	v_mfma_f32_16x16x32_bf16 v[104:107], v[158:161], v[162:165], v[104:107]
	s_waitcnt lgkmcnt(2)
	v_mfma_f32_16x16x32_bf16 v[116:119], v[158:161], v[178:181], v[116:119]
	s_waitcnt lgkmcnt(1)
	s_mov_b32 m0, s42
	v_mfma_f32_16x16x32_bf16 v[128:131], v[158:161], v[222:225], v[128:131]
	global_load_lds_dwordx4 v2, s[52:53]
	s_waitcnt lgkmcnt(0)
	v_mfma_f32_16x16x32_bf16 v[100:103], v[158:161], v[226:229], v[100:103]
	ds_read_b128 v[158:161], v7 offset:33792
	v_mfma_f32_16x16x32_bf16 v[108:111], v[166:169], v[162:165], v[108:111]
	v_mfma_f32_16x16x32_bf16 v[120:123], v[166:169], v[178:181], v[120:123]
	v_mfma_f32_16x16x32_bf16 v[132:135], v[166:169], v[222:225], v[132:135]
	s_mov_b32 m0, s43
	v_mfma_f32_16x16x32_bf16 v[140:143], v[166:169], v[226:229], v[140:143]
	global_load_lds_dwordx4 v4, s[50:51]
	ds_read_b128 v[166:169], v6 offset:1024
	v_mfma_f32_16x16x32_bf16 v[112:115], v[214:217], v[162:165], v[112:115]
	v_mfma_f32_16x16x32_bf16 v[52:55], v[218:221], v[162:165], v[52:55]
	ds_read_b128 v[162:165], v7 offset:35840
	v_mfma_f32_16x16x32_bf16 v[124:127], v[214:217], v[178:181], v[124:127]
	v_mfma_f32_16x16x32_bf16 v[68:71], v[218:221], v[178:181], v[68:71]
	ds_read_b128 v[178:181], v6 offset:3072
	s_mov_b32 m0, s44
	v_mfma_f32_16x16x32_bf16 v[136:139], v[214:217], v[222:225], v[136:139]
	global_load_lds_dwordx4 v4, s[52:53]
	v_mfma_f32_16x16x32_bf16 v[84:87], v[218:221], v[222:225], v[84:87]
	ds_read_b128 v[222:225], v6 offset:5120
	v_mfma_f32_16x16x32_bf16 v[150:153], v[214:217], v[226:229], v[150:153]
	ds_read_b128 v[214:217], v7 offset:37888
	v_mfma_f32_16x16x32_bf16 v[154:157], v[218:221], v[226:229], v[154:157]
	ds_read_b128 v[218:221], v7 offset:39936
	ds_read_b128 v[226:229], v6 offset:7168
	s_waitcnt lgkmcnt(6)
	v_mfma_f32_16x16x32_bf16 v[40:43], v[158:161], v[166:169], v[40:43]
	s_waitcnt lgkmcnt(5)
	s_mov_b32 m0, s45
	v_mfma_f32_16x16x32_bf16 v[44:47], v[162:165], v[166:169], v[44:47]
	global_load_lds_dwordx4 v146, s[50:51]
	s_waitcnt lgkmcnt(4)
	v_mfma_f32_16x16x32_bf16 v[56:59], v[158:161], v[178:181], v[56:59]
	v_mfma_f32_16x16x32_bf16 v[60:63], v[162:165], v[178:181], v[60:63]
	s_waitcnt lgkmcnt(3)
	v_mfma_f32_16x16x32_bf16 v[72:75], v[158:161], v[222:225], v[72:75]
	v_mfma_f32_16x16x32_bf16 v[76:79], v[162:165], v[222:225], v[76:79]
	s_waitcnt lgkmcnt(2)
	s_mov_b32 m0, s46
	v_mfma_f32_16x16x32_bf16 v[48:51], v[214:217], v[166:169], v[48:51]
	global_load_lds_dwordx4 v146, s[52:53]
	s_waitcnt lgkmcnt(1)
	v_mfma_f32_16x16x32_bf16 v[174:177], v[218:221], v[166:169], v[174:177]
	ds_read_b128 v[166:169], v6 offset:9216
	v_mfma_f32_16x16x32_bf16 v[64:67], v[214:217], v[178:181], v[64:67]
	v_mfma_f32_16x16x32_bf16 v[170:173], v[218:221], v[178:181], v[170:173]
	ds_read_b128 v[178:181], v6 offset:11264
	v_mfma_f32_16x16x32_bf16 v[80:83], v[214:217], v[222:225], v[80:83]
	v_mfma_f32_16x16x32_bf16 v[32:35], v[218:221], v[222:225], v[32:35]
	ds_read_b128 v[222:225], v6 offset:13312
	s_waitcnt lgkmcnt(3)
	v_mfma_f32_16x16x32_bf16 v[88:91], v[158:161], v[226:229], v[88:91]
	v_mfma_f32_16x16x32_bf16 v[92:95], v[162:165], v[226:229], v[92:95]
	v_mfma_f32_16x16x32_bf16 v[96:99], v[214:217], v[226:229], v[96:99]
	v_mfma_f32_16x16x32_bf16 v[36:39], v[218:221], v[226:229], v[36:39]
	ds_read_b128 v[226:229], v6 offset:15360
	s_waitcnt lgkmcnt(3)
	v_mfma_f32_16x16x32_bf16 v[104:107], v[158:161], v[166:169], v[104:107]
	v_mfma_f32_16x16x32_bf16 v[108:111], v[162:165], v[166:169], v[108:111]
	v_mfma_f32_16x16x32_bf16 v[112:115], v[214:217], v[166:169], v[112:115]
	v_mfma_f32_16x16x32_bf16 v[52:55], v[218:221], v[166:169], v[52:55]
	s_waitcnt lgkmcnt(2)
	v_mfma_f32_16x16x32_bf16 v[116:119], v[158:161], v[178:181], v[116:119]
	v_mfma_f32_16x16x32_bf16 v[120:123], v[162:165], v[178:181], v[120:123]
	v_mfma_f32_16x16x32_bf16 v[124:127], v[214:217], v[178:181], v[124:127]
	v_mfma_f32_16x16x32_bf16 v[68:71], v[218:221], v[178:181], v[68:71]
	s_waitcnt lgkmcnt(1)
	v_mfma_f32_16x16x32_bf16 v[128:131], v[158:161], v[222:225], v[128:131]
	v_mfma_f32_16x16x32_bf16 v[132:135], v[162:165], v[222:225], v[132:135]
	v_mfma_f32_16x16x32_bf16 v[136:139], v[214:217], v[222:225], v[136:139]
	v_mfma_f32_16x16x32_bf16 v[84:87], v[218:221], v[222:225], v[84:87]
	s_waitcnt lgkmcnt(0)
	v_mfma_f32_16x16x32_bf16 v[100:103], v[158:161], v[226:229], v[100:103]
	v_mfma_f32_16x16x32_bf16 v[140:143], v[162:165], v[226:229], v[140:143]
	v_mfma_f32_16x16x32_bf16 v[150:153], v[214:217], v[226:229], v[150:153]
	v_mfma_f32_16x16x32_bf16 v[154:157], v[218:221], v[226:229], v[154:157]
	s_add_u32 s50, s14, 0xf00
	s_addc_u32 s51, s15, 0
	s_add_u32 s52, s20, 0xf00
	s_waitcnt vmcnt(0)
	s_barrier
	s_addc_u32 s53, s21, 0
	v_lshl_add_u64 v[158:159], s[50:51], 0, v[0:1]
	s_mov_b32 s47, m0
	s_mov_b32 m0, s1
	s_nop 0
	global_load_lds_dwordx4 v[158:159], off
	s_mov_b32 m0, s47
	v_lshl_add_u64 v[158:159], s[52:53], 0, v[0:1]
	s_mov_b32 s47, m0
	s_mov_b32 m0, s34
	s_nop 0
	global_load_lds_dwordx4 v[158:159], off
	s_mov_b32 m0, s47
	v_lshl_add_u64 v[158:159], s[50:51], 0, v[2:3]
	s_mov_b32 s47, m0
	s_mov_b32 m0, s35
	s_nop 0
	global_load_lds_dwordx4 v[158:159], off
	s_mov_b32 m0, s47
	v_lshl_add_u64 v[158:159], s[52:53], 0, v[2:3]
	s_mov_b32 s47, m0
	s_mov_b32 m0, s36
	s_nop 0
	global_load_lds_dwordx4 v[158:159], off
	s_mov_b32 m0, s47
	v_lshl_add_u64 v[158:159], s[50:51], 0, v[4:5]
	s_mov_b32 s47, m0
	s_mov_b32 m0, s37
	s_nop 0
	global_load_lds_dwordx4 v[158:159], off
	s_mov_b32 m0, s47
	v_lshl_add_u64 v[158:159], s[52:53], 0, v[4:5]
	s_mov_b32 s47, m0
	s_mov_b32 m0, s38
	s_nop 0
	global_load_lds_dwordx4 v[158:159], off
	s_mov_b32 m0, s47
	v_lshl_add_u64 v[158:159], s[50:51], 0, v[146:147]
	s_mov_b32 s47, m0
	s_mov_b32 m0, s39
	s_nop 0
	global_load_lds_dwordx4 v[158:159], off
	s_mov_b32 m0, s47
	v_lshl_add_u64 v[158:159], s[52:53], 0, v[146:147]
	s_mov_b32 s47, m0
	s_mov_b32 m0, s40
	s_nop 0
	global_load_lds_dwordx4 v[158:159], off
	s_mov_b32 m0, s47
	ds_read_b128 v[158:161], v8
	ds_read_b128 v[162:165], v9
	ds_read_b128 v[166:169], v11
	ds_read_b128 v[214:217], v10
	ds_read_b128 v[178:181], v12
	ds_read_b128 v[218:221], v13
	ds_read_b128 v[222:225], v14
	ds_read_b128 v[226:229], v15
	s_waitcnt lgkmcnt(3)
	v_mfma_f32_16x16x32_bf16 v[40:43], v[158:161], v[178:181], v[40:43]
	v_mfma_f32_16x16x32_bf16 v[44:47], v[162:165], v[178:181], v[44:47]
	v_mfma_f32_16x16x32_bf16 v[48:51], v[166:169], v[178:181], v[48:51]
	v_mfma_f32_16x16x32_bf16 v[174:177], v[214:217], v[178:181], v[174:177]
	ds_read_b128 v[178:181], v16
	s_waitcnt lgkmcnt(3)
	v_mfma_f32_16x16x32_bf16 v[56:59], v[158:161], v[218:221], v[56:59]
	v_mfma_f32_16x16x32_bf16 v[60:63], v[162:165], v[218:221], v[60:63]
	v_mfma_f32_16x16x32_bf16 v[64:67], v[166:169], v[218:221], v[64:67]
	v_mfma_f32_16x16x32_bf16 v[170:173], v[214:217], v[218:221], v[170:173]
	ds_read_b128 v[218:221], v17
	s_waitcnt lgkmcnt(3)
	v_mfma_f32_16x16x32_bf16 v[72:75], v[158:161], v[222:225], v[72:75]
	v_mfma_f32_16x16x32_bf16 v[76:79], v[162:165], v[222:225], v[76:79]
	v_mfma_f32_16x16x32_bf16 v[80:83], v[166:169], v[222:225], v[80:83]
	v_mfma_f32_16x16x32_bf16 v[32:35], v[214:217], v[222:225], v[32:35]
	ds_read_b128 v[222:225], v18
	s_waitcnt lgkmcnt(3)
	v_mfma_f32_16x16x32_bf16 v[88:91], v[158:161], v[226:229], v[88:91]
	v_mfma_f32_16x16x32_bf16 v[92:95], v[162:165], v[226:229], v[92:95]
	v_mfma_f32_16x16x32_bf16 v[96:99], v[166:169], v[226:229], v[96:99]
	v_mfma_f32_16x16x32_bf16 v[36:39], v[214:217], v[226:229], v[36:39]
	ds_read_b128 v[226:229], v19
	s_waitcnt lgkmcnt(3)
	v_mfma_f32_16x16x32_bf16 v[104:107], v[158:161], v[178:181], v[104:107]
	v_mfma_f32_16x16x32_bf16 v[108:111], v[162:165], v[178:181], v[108:111]
	v_mfma_f32_16x16x32_bf16 v[112:115], v[166:169], v[178:181], v[112:115]
	v_mfma_f32_16x16x32_bf16 v[52:55], v[214:217], v[178:181], v[52:55]
	s_waitcnt lgkmcnt(2)
	v_mfma_f32_16x16x32_bf16 v[116:119], v[158:161], v[218:221], v[116:119]
	v_mfma_f32_16x16x32_bf16 v[120:123], v[162:165], v[218:221], v[120:123]
	v_mfma_f32_16x16x32_bf16 v[124:127], v[166:169], v[218:221], v[124:127]
	v_mfma_f32_16x16x32_bf16 v[68:71], v[214:217], v[218:221], v[68:71]
	s_waitcnt lgkmcnt(1)
	v_mfma_f32_16x16x32_bf16 v[132:135], v[162:165], v[222:225], v[132:135]
	v_mfma_f32_16x16x32_bf16 v[84:87], v[214:217], v[222:225], v[84:87]
	s_waitcnt lgkmcnt(0)
	v_mfma_f32_16x16x32_bf16 v[100:103], v[158:161], v[226:229], v[100:103]
	v_mfma_f32_16x16x32_bf16 v[150:153], v[166:169], v[226:229], v[150:153]
	v_mfma_f32_16x16x32_bf16 v[154:157], v[214:217], v[226:229], v[154:157]
	v_mfma_f32_16x16x32_bf16 v[128:131], v[158:161], v[222:225], v[128:131]
	v_mfma_f32_16x16x32_bf16 v[136:139], v[166:169], v[222:225], v[136:139]
	v_mfma_f32_16x16x32_bf16 v[140:143], v[162:165], v[226:229], v[140:143]
	ds_read_b128 v[158:161], v20
	ds_read_b128 v[162:165], v21
	ds_read_b128 v[166:169], v23
	ds_read_b128 v[214:217], v22
	ds_read_b128 v[178:181], v24
	ds_read_b128 v[218:221], v25
	ds_read_b128 v[222:225], v26
	ds_read_b128 v[226:229], v27
	s_waitcnt lgkmcnt(3)
	v_mfma_f32_16x16x32_bf16 v[40:43], v[158:161], v[178:181], v[40:43]
	v_mfma_f32_16x16x32_bf16 v[44:47], v[162:165], v[178:181], v[44:47]
	v_mfma_f32_16x16x32_bf16 v[48:51], v[166:169], v[178:181], v[48:51]
	v_mfma_f32_16x16x32_bf16 v[174:177], v[214:217], v[178:181], v[174:177]
	ds_read_b128 v[178:181], v28
	s_waitcnt lgkmcnt(3)
	v_mfma_f32_16x16x32_bf16 v[56:59], v[158:161], v[218:221], v[56:59]
	v_mfma_f32_16x16x32_bf16 v[60:63], v[162:165], v[218:221], v[60:63]
	v_mfma_f32_16x16x32_bf16 v[64:67], v[166:169], v[218:221], v[64:67]
	v_mfma_f32_16x16x32_bf16 v[170:173], v[214:217], v[218:221], v[170:173]
	ds_read_b128 v[218:221], v29
	s_waitcnt lgkmcnt(3)
	v_mfma_f32_16x16x32_bf16 v[72:75], v[158:161], v[222:225], v[72:75]
	v_mfma_f32_16x16x32_bf16 v[76:79], v[162:165], v[222:225], v[76:79]
	v_mfma_f32_16x16x32_bf16 v[80:83], v[166:169], v[222:225], v[80:83]
	v_mfma_f32_16x16x32_bf16 v[32:35], v[214:217], v[222:225], v[32:35]
	ds_read_b128 v[222:225], v30
	s_waitcnt lgkmcnt(3)
	v_mfma_f32_16x16x32_bf16 v[88:91], v[158:161], v[226:229], v[88:91]
	v_mfma_f32_16x16x32_bf16 v[92:95], v[162:165], v[226:229], v[92:95]
	v_mfma_f32_16x16x32_bf16 v[96:99], v[166:169], v[226:229], v[96:99]
	v_mfma_f32_16x16x32_bf16 v[36:39], v[214:217], v[226:229], v[36:39]
	ds_read_b128 v[226:229], v31
	s_waitcnt lgkmcnt(3)
	v_mfma_f32_16x16x32_bf16 v[104:107], v[158:161], v[178:181], v[104:107]
	v_mfma_f32_16x16x32_bf16 v[108:111], v[162:165], v[178:181], v[108:111]
	v_mfma_f32_16x16x32_bf16 v[112:115], v[166:169], v[178:181], v[112:115]
	v_mfma_f32_16x16x32_bf16 v[52:55], v[214:217], v[178:181], v[52:55]
	s_waitcnt lgkmcnt(2)
	v_mfma_f32_16x16x32_bf16 v[116:119], v[158:161], v[218:221], v[116:119]
	v_mfma_f32_16x16x32_bf16 v[120:123], v[162:165], v[218:221], v[120:123]
	v_mfma_f32_16x16x32_bf16 v[124:127], v[166:169], v[218:221], v[124:127]
	v_mfma_f32_16x16x32_bf16 v[68:71], v[214:217], v[218:221], v[68:71]
	s_waitcnt lgkmcnt(1)
	v_mfma_f32_16x16x32_bf16 v[132:135], v[162:165], v[222:225], v[132:135]
	v_mfma_f32_16x16x32_bf16 v[84:87], v[214:217], v[222:225], v[84:87]
	s_waitcnt lgkmcnt(0)
	v_mfma_f32_16x16x32_bf16 v[100:103], v[158:161], v[226:229], v[100:103]
	v_mfma_f32_16x16x32_bf16 v[150:153], v[166:169], v[226:229], v[150:153]
	v_mfma_f32_16x16x32_bf16 v[154:157], v[214:217], v[226:229], v[154:157]
	v_mfma_f32_16x16x32_bf16 v[128:131], v[158:161], v[222:225], v[128:131]
	v_mfma_f32_16x16x32_bf16 v[136:139], v[166:169], v[222:225], v[136:139]
	v_mfma_f32_16x16x32_bf16 v[140:143], v[162:165], v[226:229], v[140:143]
	s_add_u32 s14, s14, 0xf80
	s_addc_u32 s15, s15, 0
	s_add_u32 s20, s20, 0xf80
	s_waitcnt vmcnt(0)
	s_barrier
	s_addc_u32 s21, s21, 0
	v_lshl_add_u64 v[158:159], s[14:15], 0, v[0:1]
	s_mov_b32 s47, m0
	s_mov_b32 m0, s27
	s_nop 0
	global_load_lds_dwordx4 v[158:159], off
	s_mov_b32 m0, s47
	v_lshl_add_u64 v[158:159], s[20:21], 0, v[0:1]
	s_mov_b32 s27, m0
	s_mov_b32 m0, s26
	s_nop 0
	global_load_lds_dwordx4 v[158:159], off
	s_mov_b32 m0, s27
	v_lshl_add_u64 v[158:159], s[14:15], 0, v[2:3]
	s_mov_b32 s26, m0
	s_mov_b32 m0, s41
	s_nop 0
	global_load_lds_dwordx4 v[158:159], off
	s_mov_b32 m0, s26
	v_lshl_add_u64 v[158:159], s[20:21], 0, v[2:3]
	s_mov_b32 s26, m0
	s_mov_b32 m0, s42
	s_nop 0
	global_load_lds_dwordx4 v[158:159], off
	s_mov_b32 m0, s26
	v_lshl_add_u64 v[158:159], s[14:15], 0, v[4:5]
	s_mov_b32 s26, m0
	s_mov_b32 m0, s43
	s_nop 0
	global_load_lds_dwordx4 v[158:159], off
	s_mov_b32 m0, s26
	v_lshl_add_u64 v[158:159], s[20:21], 0, v[4:5]
	s_mov_b32 s26, m0
	s_mov_b32 m0, s44
	s_nop 0
	global_load_lds_dwordx4 v[158:159], off
	s_mov_b32 m0, s26
	v_lshl_add_u64 v[158:159], s[14:15], 0, v[146:147]
	s_mov_b32 s14, m0
	s_mov_b32 m0, s45
	s_nop 0
	global_load_lds_dwordx4 v[158:159], off
	s_mov_b32 m0, s14
	v_lshl_add_u64 v[158:159], s[20:21], 0, v[146:147]
	s_mov_b32 s14, m0
	s_mov_b32 m0, s46
	s_nop 0
	global_load_lds_dwordx4 v[158:159], off
	s_mov_b32 m0, s14
	ds_read_b128 v[158:161], v7 offset:32768
	ds_read_b128 v[162:165], v7 offset:34816
	ds_read_b128 v[166:169], v7 offset:36864
	ds_read_b128 v[214:217], v7 offset:38912
	ds_read_b128 v[178:181], v6
	ds_read_b128 v[218:221], v6 offset:2048
	ds_read_b128 v[222:225], v6 offset:4096
	ds_read_b128 v[226:229], v6 offset:6144
	s_waitcnt lgkmcnt(3)
	v_mfma_f32_16x16x32_bf16 v[40:43], v[158:161], v[178:181], v[40:43]
	v_mfma_f32_16x16x32_bf16 v[44:47], v[162:165], v[178:181], v[44:47]
	v_mfma_f32_16x16x32_bf16 v[48:51], v[166:169], v[178:181], v[48:51]
	v_mfma_f32_16x16x32_bf16 v[174:177], v[214:217], v[178:181], v[174:177]
	ds_read_b128 v[178:181], v6 offset:8192
	s_waitcnt lgkmcnt(3)
	v_mfma_f32_16x16x32_bf16 v[56:59], v[158:161], v[218:221], v[56:59]
	v_mfma_f32_16x16x32_bf16 v[60:63], v[162:165], v[218:221], v[60:63]
	v_mfma_f32_16x16x32_bf16 v[64:67], v[166:169], v[218:221], v[64:67]
	v_mfma_f32_16x16x32_bf16 v[170:173], v[214:217], v[218:221], v[170:173]
	ds_read_b128 v[218:221], v6 offset:10240
	s_waitcnt lgkmcnt(3)
	v_mfma_f32_16x16x32_bf16 v[72:75], v[158:161], v[222:225], v[72:75]
	v_mfma_f32_16x16x32_bf16 v[76:79], v[162:165], v[222:225], v[76:79]
	v_mfma_f32_16x16x32_bf16 v[80:83], v[166:169], v[222:225], v[80:83]
	v_mfma_f32_16x16x32_bf16 v[32:35], v[214:217], v[222:225], v[32:35]
	ds_read_b128 v[222:225], v6 offset:12288
	s_waitcnt lgkmcnt(3)
	v_mfma_f32_16x16x32_bf16 v[88:91], v[158:161], v[226:229], v[88:91]
	v_mfma_f32_16x16x32_bf16 v[92:95], v[162:165], v[226:229], v[92:95]
	v_mfma_f32_16x16x32_bf16 v[96:99], v[166:169], v[226:229], v[96:99]
	v_mfma_f32_16x16x32_bf16 v[36:39], v[214:217], v[226:229], v[36:39]
	ds_read_b128 v[226:229], v6 offset:14336
	s_waitcnt lgkmcnt(3)
	v_mfma_f32_16x16x32_bf16 v[104:107], v[158:161], v[178:181], v[104:107]
	v_mfma_f32_16x16x32_bf16 v[108:111], v[162:165], v[178:181], v[108:111]
	v_mfma_f32_16x16x32_bf16 v[112:115], v[166:169], v[178:181], v[112:115]
	v_mfma_f32_16x16x32_bf16 v[52:55], v[214:217], v[178:181], v[52:55]
	s_waitcnt lgkmcnt(2)
	v_mfma_f32_16x16x32_bf16 v[116:119], v[158:161], v[218:221], v[116:119]
	v_mfma_f32_16x16x32_bf16 v[120:123], v[162:165], v[218:221], v[120:123]
	v_mfma_f32_16x16x32_bf16 v[124:127], v[166:169], v[218:221], v[124:127]
	v_mfma_f32_16x16x32_bf16 v[68:71], v[214:217], v[218:221], v[68:71]
	s_waitcnt lgkmcnt(1)
	v_mfma_f32_16x16x32_bf16 v[132:135], v[162:165], v[222:225], v[132:135]
	v_mfma_f32_16x16x32_bf16 v[84:87], v[214:217], v[222:225], v[84:87]
	s_waitcnt lgkmcnt(0)
	v_mfma_f32_16x16x32_bf16 v[100:103], v[158:161], v[226:229], v[100:103]
	v_mfma_f32_16x16x32_bf16 v[150:153], v[166:169], v[226:229], v[150:153]
	v_mfma_f32_16x16x32_bf16 v[154:157], v[214:217], v[226:229], v[154:157]
	v_mfma_f32_16x16x32_bf16 v[128:131], v[158:161], v[222:225], v[128:131]
	v_mfma_f32_16x16x32_bf16 v[136:139], v[166:169], v[222:225], v[136:139]
	v_mfma_f32_16x16x32_bf16 v[140:143], v[162:165], v[226:229], v[140:143]
	ds_read_b128 v[158:161], v7 offset:33792
	ds_read_b128 v[162:165], v7 offset:35840
	ds_read_b128 v[166:169], v7 offset:37888
	ds_read_b128 v[214:217], v7 offset:39936
	ds_read_b128 v[178:181], v6 offset:1024
	ds_read_b128 v[218:221], v6 offset:3072
	ds_read_b128 v[222:225], v6 offset:5120
	ds_read_b128 v[226:229], v6 offset:7168
	s_waitcnt lgkmcnt(3)
	v_mfma_f32_16x16x32_bf16 v[40:43], v[158:161], v[178:181], v[40:43]
	v_mfma_f32_16x16x32_bf16 v[44:47], v[162:165], v[178:181], v[44:47]
	v_mfma_f32_16x16x32_bf16 v[48:51], v[166:169], v[178:181], v[48:51]
	v_mfma_f32_16x16x32_bf16 v[174:177], v[214:217], v[178:181], v[174:177]
	ds_read_b128 v[178:181], v6 offset:9216
	s_waitcnt lgkmcnt(3)
	v_mfma_f32_16x16x32_bf16 v[56:59], v[158:161], v[218:221], v[56:59]
	v_mfma_f32_16x16x32_bf16 v[60:63], v[162:165], v[218:221], v[60:63]
	v_mfma_f32_16x16x32_bf16 v[64:67], v[166:169], v[218:221], v[64:67]
	v_mfma_f32_16x16x32_bf16 v[170:173], v[214:217], v[218:221], v[170:173]
	ds_read_b128 v[218:221], v6 offset:11264
	s_waitcnt lgkmcnt(3)
	v_mfma_f32_16x16x32_bf16 v[72:75], v[158:161], v[222:225], v[72:75]
	v_mfma_f32_16x16x32_bf16 v[76:79], v[162:165], v[222:225], v[76:79]
	v_mfma_f32_16x16x32_bf16 v[80:83], v[166:169], v[222:225], v[80:83]
	v_mfma_f32_16x16x32_bf16 v[32:35], v[214:217], v[222:225], v[32:35]
	ds_read_b128 v[222:225], v6 offset:13312
	s_waitcnt lgkmcnt(3)
	v_mfma_f32_16x16x32_bf16 v[88:91], v[158:161], v[226:229], v[88:91]
	v_mfma_f32_16x16x32_bf16 v[92:95], v[162:165], v[226:229], v[92:95]
	v_mfma_f32_16x16x32_bf16 v[96:99], v[166:169], v[226:229], v[96:99]
	v_mfma_f32_16x16x32_bf16 v[36:39], v[214:217], v[226:229], v[36:39]
	ds_read_b128 v[226:229], v6 offset:15360
	s_waitcnt lgkmcnt(3)
	v_mfma_f32_16x16x32_bf16 v[104:107], v[158:161], v[178:181], v[104:107]
	v_mfma_f32_16x16x32_bf16 v[108:111], v[162:165], v[178:181], v[108:111]
	v_mfma_f32_16x16x32_bf16 v[112:115], v[166:169], v[178:181], v[112:115]
	v_mfma_f32_16x16x32_bf16 v[52:55], v[214:217], v[178:181], v[52:55]
	s_waitcnt lgkmcnt(2)
	v_mfma_f32_16x16x32_bf16 v[116:119], v[158:161], v[218:221], v[116:119]
	v_mfma_f32_16x16x32_bf16 v[120:123], v[162:165], v[218:221], v[120:123]
	v_mfma_f32_16x16x32_bf16 v[124:127], v[166:169], v[218:221], v[124:127]
	v_mfma_f32_16x16x32_bf16 v[68:71], v[214:217], v[218:221], v[68:71]
	s_waitcnt lgkmcnt(1)
	v_mfma_f32_16x16x32_bf16 v[132:135], v[162:165], v[222:225], v[132:135]
	v_mfma_f32_16x16x32_bf16 v[84:87], v[214:217], v[222:225], v[84:87]
	s_waitcnt lgkmcnt(0)
	v_mfma_f32_16x16x32_bf16 v[100:103], v[158:161], v[226:229], v[100:103]
	v_mfma_f32_16x16x32_bf16 v[150:153], v[166:169], v[226:229], v[150:153]
	v_mfma_f32_16x16x32_bf16 v[154:157], v[214:217], v[226:229], v[154:157]
	v_mfma_f32_16x16x32_bf16 v[128:131], v[158:161], v[222:225], v[128:131]
	v_mfma_f32_16x16x32_bf16 v[136:139], v[166:169], v[222:225], v[136:139]
	v_mfma_f32_16x16x32_bf16 v[140:143], v[162:165], v[226:229], v[140:143]
	s_waitcnt vmcnt(0)
	s_barrier
	v_lshl_add_u64 v[6:7], s[22:23], 0, v[0:1]
	s_mov_b32 s14, m0
	s_mov_b32 m0, s1
	s_nop 0
	global_load_lds_dwordx4 v[6:7], off
	s_mov_b32 m0, s14
	v_lshl_add_u64 v[0:1], s[24:25], 0, v[0:1]
	s_mov_b32 s1, m0
	s_mov_b32 m0, s34
	s_nop 0
	global_load_lds_dwordx4 v[0:1], off
	s_mov_b32 m0, s1
	v_lshl_add_u64 v[0:1], s[22:23], 0, v[2:3]
	s_mov_b32 s1, m0
	s_mov_b32 m0, s35
	s_nop 0
	global_load_lds_dwordx4 v[0:1], off
	s_mov_b32 m0, s1
	v_lshl_add_u64 v[0:1], s[24:25], 0, v[2:3]
	s_mov_b32 s1, m0
	s_mov_b32 m0, s36
	s_nop 0
	global_load_lds_dwordx4 v[0:1], off
	s_mov_b32 m0, s1
	v_lshl_add_u64 v[0:1], s[22:23], 0, v[4:5]
	s_mov_b32 s1, m0
	s_mov_b32 m0, s37
	s_nop 0
	global_load_lds_dwordx4 v[0:1], off
	s_mov_b32 m0, s1
	v_lshl_add_u64 v[0:1], s[24:25], 0, v[4:5]
	s_mov_b32 s1, m0
	s_mov_b32 m0, s38
	s_nop 0
	global_load_lds_dwordx4 v[0:1], off
	s_mov_b32 m0, s1
	v_lshl_add_u64 v[0:1], s[22:23], 0, v[146:147]
	s_mov_b32 s1, m0
	s_mov_b32 m0, s39
	s_nop 0
	global_load_lds_dwordx4 v[0:1], off
	s_mov_b32 m0, s1
	v_lshl_add_u64 v[0:1], s[24:25], 0, v[146:147]
	s_mov_b32 s1, m0
	s_mov_b32 m0, s40
	s_nop 0
	global_load_lds_dwordx4 v[0:1], off
	s_mov_b32 m0, s1
	ds_read_b128 v[0:3], v8
	ds_read_b128 v[4:7], v9
	ds_read_b128 v[158:161], v11
	ds_read_b128 v[8:11], v10
	ds_read_b128 v[162:165], v12
	ds_read_b128 v[166:169], v13
	ds_read_b128 v[178:181], v14
	ds_read_b128 v[12:15], v15
	s_waitcnt lgkmcnt(3)
	v_mfma_f32_16x16x32_bf16 v[40:43], v[0:3], v[162:165], v[40:43]
	v_mfma_f32_16x16x32_bf16 v[44:47], v[4:7], v[162:165], v[44:47]
	v_mfma_f32_16x16x32_bf16 v[48:51], v[158:161], v[162:165], v[48:51]
	v_mfma_f32_16x16x32_bf16 v[162:165], v[8:11], v[162:165], v[174:177]
	s_nop 2
	ds_read_b128 v[174:177], v16
	s_waitcnt lgkmcnt(3)
	v_mfma_f32_16x16x32_bf16 v[56:59], v[0:3], v[166:169], v[56:59]
	v_mfma_f32_16x16x32_bf16 v[60:63], v[4:7], v[166:169], v[60:63]
	v_mfma_f32_16x16x32_bf16 v[64:67], v[158:161], v[166:169], v[64:67]
	v_mfma_f32_16x16x32_bf16 v[166:169], v[8:11], v[166:169], v[170:173]
	s_nop 2
	ds_read_b128 v[170:173], v17
	s_waitcnt lgkmcnt(3)
	v_mfma_f32_16x16x32_bf16 v[72:75], v[0:3], v[178:181], v[72:75]
	v_mfma_f32_16x16x32_bf16 v[76:79], v[4:7], v[178:181], v[76:79]
	v_mfma_f32_16x16x32_bf16 v[80:83], v[158:161], v[178:181], v[80:83]
	v_mfma_f32_16x16x32_bf16 v[32:35], v[8:11], v[178:181], v[32:35]
	ds_read_b128 v[178:181], v18
	s_waitcnt lgkmcnt(3)
	v_mfma_f32_16x16x32_bf16 v[214:217], v[0:3], v[12:15], v[88:91]
	v_mfma_f32_16x16x32_bf16 v[218:221], v[4:7], v[12:15], v[92:95]
	v_mfma_f32_16x16x32_bf16 v[222:225], v[158:161], v[12:15], v[96:99]
	v_mfma_f32_16x16x32_bf16 v[12:15], v[8:11], v[12:15], v[36:39]
	ds_read_b128 v[16:19], v19
	s_waitcnt lgkmcnt(3)
	v_mfma_f32_16x16x32_bf16 v[36:39], v[0:3], v[174:177], v[104:107]
	v_mfma_f32_16x16x32_bf16 v[226:229], v[4:7], v[174:177], v[108:111]
	v_mfma_f32_16x16x32_bf16 v[112:115], v[158:161], v[174:177], v[112:115]
	s_waitcnt lgkmcnt(2)
	v_mfma_f32_16x16x32_bf16 v[116:119], v[0:3], v[170:173], v[116:119]
	v_mfma_f32_16x16x32_bf16 v[120:123], v[4:7], v[170:173], v[120:123]
	v_mfma_f32_16x16x32_bf16 v[124:127], v[158:161], v[170:173], v[124:127]
	s_waitcnt lgkmcnt(1)
	v_mfma_f32_16x16x32_bf16 v[128:131], v[0:3], v[178:181], v[128:131]
	v_mfma_f32_16x16x32_bf16 v[132:135], v[4:7], v[178:181], v[132:135]
	s_waitcnt lgkmcnt(0)
	v_mfma_f32_16x16x32_bf16 v[0:3], v[0:3], v[16:19], v[100:103]
	v_mfma_f32_16x16x32_bf16 v[4:7], v[4:7], v[16:19], v[140:143]
	v_mfma_f32_16x16x32_bf16 v[140:143], v[158:161], v[16:19], v[150:153]
	v_mfma_f32_16x16x32_bf16 v[150:153], v[8:11], v[16:19], v[154:157]
	v_mfma_f32_16x16x32_bf16 v[174:177], v[8:11], v[174:177], v[52:55]
	v_mfma_f32_16x16x32_bf16 v[170:173], v[8:11], v[170:173], v[68:71]
	v_mfma_f32_16x16x32_bf16 v[136:139], v[158:161], v[178:181], v[136:139]
	v_mfma_f32_16x16x32_bf16 v[178:181], v[8:11], v[178:181], v[84:87]
	ds_read_b128 v[8:11], v20
	ds_read_b128 v[154:157], v21
	ds_read_b128 v[158:161], v23
	ds_read_b128 v[230:233], v22
	ds_read_b128 v[16:19], v24
	ds_read_b128 v[20:23], v25
	ds_read_b128 v[52:55], v26
	ds_read_b128 v[24:27], v27
	s_waitcnt lgkmcnt(3)
	v_mfma_f32_16x16x32_bf16 v[234:237], v[8:11], v[16:19], v[40:43]
	v_mfma_f32_16x16x32_bf16 v[238:241], v[154:157], v[16:19], v[44:47]
	v_mfma_f32_16x16x32_bf16 v[242:245], v[158:161], v[16:19], v[48:51]
	v_mfma_f32_16x16x32_bf16 v[162:165], v[230:233], v[16:19], v[162:165]
	ds_read_b128 v[16:19], v28
	s_waitcnt lgkmcnt(3)
	v_mfma_f32_16x16x32_bf16 v[108:111], v[8:11], v[20:23], v[56:59]
	v_mfma_f32_16x16x32_bf16 v[104:107], v[154:157], v[20:23], v[60:63]
	v_mfma_f32_16x16x32_bf16 v[100:103], v[158:161], v[20:23], v[64:67]
	v_mfma_f32_16x16x32_bf16 v[96:99], v[230:233], v[20:23], v[166:169]
	ds_read_b128 v[20:23], v29
	s_waitcnt lgkmcnt(3)
	v_mfma_f32_16x16x32_bf16 v[92:95], v[8:11], v[52:55], v[72:75]
	v_mfma_f32_16x16x32_bf16 v[88:91], v[154:157], v[52:55], v[76:79]
	v_mfma_f32_16x16x32_bf16 v[84:87], v[158:161], v[52:55], v[80:83]
	v_mfma_f32_16x16x32_bf16 v[80:83], v[230:233], v[52:55], v[32:35]
	ds_read_b128 v[166:169], v30
	s_waitcnt lgkmcnt(3)
	v_mfma_f32_16x16x32_bf16 v[76:79], v[8:11], v[24:27], v[214:217]
	v_mfma_f32_16x16x32_bf16 v[72:75], v[154:157], v[24:27], v[218:221]
	v_mfma_f32_16x16x32_bf16 v[68:71], v[158:161], v[24:27], v[222:225]
	v_mfma_f32_16x16x32_bf16 v[64:67], v[230:233], v[24:27], v[12:15]
	ds_read_b128 v[214:217], v31
	s_waitcnt lgkmcnt(3)
	v_mfma_f32_16x16x32_bf16 v[60:63], v[8:11], v[16:19], v[36:39]
	v_mfma_f32_16x16x32_bf16 v[56:59], v[154:157], v[16:19], v[226:229]
	v_mfma_f32_16x16x32_bf16 v[52:55], v[158:161], v[16:19], v[112:115]
	v_mfma_f32_16x16x32_bf16 v[48:51], v[230:233], v[16:19], v[174:177]
	s_waitcnt lgkmcnt(2)
	v_mfma_f32_16x16x32_bf16 v[44:47], v[8:11], v[20:23], v[116:119]
	v_mfma_f32_16x16x32_bf16 v[40:43], v[154:157], v[20:23], v[120:123]
	v_mfma_f32_16x16x32_bf16 v[36:39], v[158:161], v[20:23], v[124:127]
	v_mfma_f32_16x16x32_bf16 v[32:35], v[230:233], v[20:23], v[170:173]
	s_waitcnt lgkmcnt(1)
	v_mfma_f32_16x16x32_bf16 v[28:31], v[8:11], v[166:169], v[128:131]
	v_mfma_f32_16x16x32_bf16 v[24:27], v[154:157], v[166:169], v[132:135]
	v_mfma_f32_16x16x32_bf16 v[20:23], v[158:161], v[166:169], v[136:139]
	v_mfma_f32_16x16x32_bf16 v[16:19], v[230:233], v[166:169], v[178:181]
	s_waitcnt lgkmcnt(0)
	v_mfma_f32_16x16x32_bf16 v[12:15], v[8:11], v[214:217], v[0:3]
	v_mfma_f32_16x16x32_bf16 v[8:11], v[154:157], v[214:217], v[4:7]
	v_mfma_f32_16x16x32_bf16 v[4:7], v[158:161], v[214:217], v[140:143]
	v_mfma_f32_16x16x32_bf16 v[0:3], v[230:233], v[214:217], v[150:153]
	v_mov_b32_e32 v145, v184
	s_waitcnt vmcnt(0)
	s_barrier
	s_lshl_b32 s20, s0, 8
	s_lshl_b32 s14, s12, 8
	v_and_b32_e32 v151, 15, v145
	v_ashrrev_i32_e32 v112, 1, v145
	v_and_b32_e32 v153, 0xffffff80, v112
	v_or_b32_e32 v112, s20, v151
	v_add_u32_e32 v112, v112, v153
	v_ashrrev_i32_e32 v113, 31, v112
	v_lshlrev_b64 v[112:113], 13, v[112:113]
	v_bfe_u32 v150, v145, 6, 2
	v_lshl_add_u64 v[112:113], s[2:3], 0, v[112:113]
	s_ashr_i32 s15, s14, 31
	v_bfe_u32 v152, v145, 4, 2
	v_lshl_add_u64 v[112:113], s[14:15], 2, v[112:113]
	v_lshlrev_b32_e32 v146, 8, v150
	v_lshl_add_u64 v[112:113], v[112:113], 0, v[146:147]
	v_lshlrev_b32_e32 v146, 4, v152
	v_lshl_add_u64 v[154:155], v[112:113], 0, v[146:147]
	global_load_dwordx4 v[120:123], v[154:155], off offset:192
	global_load_dwordx4 v[128:131], v[154:155], off offset:128
	global_load_dwordx4 v[136:139], v[154:155], off offset:64
	global_load_dwordx4 v[140:143], v[154:155], off
	v_add_co_u32_e32 v112, vcc, s66, v154
	v_lshlrev_b32_e32 v158, 2, v152
	s_nop 0
	v_addc_co_u32_e32 v113, vcc, 0, v155, vcc
	global_load_dwordx4 v[132:135], v[112:113], off
	global_load_dwordx4 v[124:127], v[112:113], off offset:64
	global_load_dwordx4 v[116:119], v[112:113], off offset:128
	v_cmp_lt_i32_e32 vcc, v188, v186
	global_load_dwordx4 v[112:115], v[112:113], off offset:192
	v_cmp_eq_u32_e64 s[0:1], 0, v152
	v_cndmask_b32_e32 v146, v185, v188, vcc
	v_cmp_lt_i32_e32 vcc, v187, v186
	v_lshlrev_b32_e32 v149, 2, v146
	v_lshlrev_b32_e32 v157, 6, v150
	v_cndmask_b32_e32 v156, v185, v187, vcc
	v_lshlrev_b32_e32 v146, 2, v156
	v_or_b32_e32 v156, v153, v151
	v_add_u32_e32 v152, s20, v156
	v_ashrrev_i32_e32 v153, 31, v152
	v_lshl_or_b32 v182, v150, 10, v204
	v_or3_b32 v150, v157, s14, v158
	v_lshlrev_b64 v[158:159], 13, v[152:153]
	v_ashrrev_i32_e32 v151, 31, v150
	v_lshlrev_b64 v[160:161], 12, v[152:153]
	v_lshl_add_u64 v[158:159], s[2:3], 0, v[158:159]
	v_lshl_add_u64 v[160:161], s[4:5], 0, v[160:161]
	v_lshl_add_u64 v[166:167], v[150:151], 2, v[158:159]
	v_lshl_add_u64 v[168:169], v[150:151], 1, v[160:161]
	s_waitcnt vmcnt(7)
	v_pk_add_f32 v[158:159], v[162:163], v[120:121]
	s_waitcnt vmcnt(6)
	v_pk_add_f32 v[120:121], v[242:243], v[128:129]
	s_waitcnt vmcnt(5)
	v_pk_add_f32 v[128:129], v[238:239], v[136:137]
	s_waitcnt vmcnt(4)
	v_pk_add_f32 v[136:137], v[234:235], v[140:141]
	v_pk_add_f32 v[160:161], v[164:165], v[122:123]
	v_pk_add_f32 v[122:123], v[244:245], v[130:131]
	v_pk_add_f32 v[130:131], v[240:241], v[138:139]
	v_pk_add_f32 v[138:139], v[236:237], v[142:143]
	v_pk_mul_f32 v[172:173], v[128:129], v[128:129]
	v_pk_mul_f32 v[178:179], v[136:137], v[136:137]
	v_pk_mul_f32 v[162:163], v[120:121], v[120:121]
	v_pk_mul_f32 v[174:175], v[130:131], v[130:131]
	v_cvt_pk_bf16_f32 v176, v136, v137
	v_pk_mul_f32 v[180:181], v[138:139], v[138:139]
	global_store_dwordx4 v[166:167], v[136:139], off
	v_add_f32_e32 v153, v172, v173
	v_add_f32_e32 v157, v178, v179
	v_pk_mul_f32 v[136:137], v[158:159], v[158:159]
	v_pk_mul_f32 v[164:165], v[122:123], v[122:123]
	v_cvt_pk_bf16_f32 v177, v138, v139
	v_pk_mul_f32 v[138:139], v[160:161], v[160:161]
	v_add_f32_e32 v162, v162, v163
	v_add_f32_e32 v136, v136, v137
	v_add_f32_e32 v137, v174, v153
	v_add_f32_e32 v153, v180, v157
	v_add_f32_e32 v157, v164, v162
	v_add_f32_e32 v136, v138, v136
	v_add_f32_e32 v137, v175, v137
	v_add_f32_e32 v138, v181, v153
	v_add_f32_e32 v153, v165, v157
	v_add_f32_e32 v137, v138, v137
	v_add_f32_e32 v137, v137, v153
	v_add_f32_e32 v136, v139, v136
	v_add_f32_e32 v136, v137, v136
	ds_bpermute_b32 v137, v149, v136
	v_cvt_pk_bf16_f32 v170, v128, v129
	v_cvt_pk_bf16_f32 v171, v130, v131
	v_cvt_pk_bf16_f32 v142, v120, v121
	global_store_dwordx2 v[168:169], v[176:177], off
	global_store_dwordx4 v[166:167], v[128:131], off offset:64
	global_store_dwordx2 v[168:169], v[170:171], off offset:32
	global_store_dwordx4 v[166:167], v[120:123], off offset:128
	v_cvt_pk_bf16_f32 v140, v158, v159
	v_cvt_pk_bf16_f32 v141, v160, v161
	s_waitcnt lgkmcnt(0)
	v_add_f32_e32 v120, v136, v137
	ds_bpermute_b32 v121, v146, v120
	v_cvt_pk_bf16_f32 v143, v122, v123
	v_lshl_add_u32 v153, v156, 2, v182
	global_store_dwordx2 v[168:169], v[142:143], off offset:64
	global_store_dwordx4 v[166:167], v[158:161], off offset:192
	global_store_dwordx2 v[168:169], v[140:141], off offset:96
	s_and_saveexec_b64 s[14:15], s[0:1]
	s_cbranch_execz .LBB0_698
	s_waitcnt lgkmcnt(0)
	v_add_f32_e32 v120, v120, v121
	ds_write_b32 v153, v120

.LBB0_757:
	s_ashr_i32 s25, s24, 31
	s_lshl_b64 s[24:25], s[24:25], 20
	s_add_u32 s27, s2, s24
	s_addc_u32 s45, s3, s25
	s_ashr_i32 s47, s46, 1
	s_lshl_b32 s24, s47, 8
	s_ashr_i32 s25, s24, 31
	s_lshl_b64 s[24:25], s[24:25], 1
	s_add_u32 s27, s27, s24
	s_addc_u32 s45, s45, s25
	s_add_i32 s24, s47, s28
	s_ashr_i32 s25, s24, 31
	s_lshl_b64 s[24:25], s[24:25], 18
	s_add_u32 s24, s29, s24
	s_addc_u32 s25, s30, s25
	s_lshl_b32 s46, s46, 17
	v_lshlrev_b32_e32 v3, 6, v1
	s_and_b32 s46, s46, 0x20000
	v_and_b32_e32 v2, 48, v1
	v_and_b32_e32 v4, 0x3c0, v3
	v_lshlrev_b32_e32 v1, 2, v1
	s_add_u32 s46, s24, s46
	v_or_b32_e32 v5, v4, v2
	v_and_b32_e32 v1, 32, v1
	v_lshlrev_b32_e32 v0, 13, v0
	s_mov_b32 s24, 0x18000
	v_and_b32_e32 v143, 0x6000, v0
	v_bitop3_b32 v0, v5, s24, v1 bitop3:0xde
	s_mov_b32 s24, 0x10400
	s_addc_u32 s47, s25, 0
	v_bitop3_b32 v157, v5, s24, v1 bitop3:0xde
	s_add_i32 s24, s31, s63
	s_ashr_i32 s25, s24, 31
	s_lshl_b32 s62, s62, 15
	s_lshl_b64 s[24:25], s[24:25], 18
	s_and_b32 s62, s62, 0x20000
	s_add_i32 s49, s38, 0x10000
	s_add_i32 s50, s38, 0x18000
	s_add_i32 s51, s38, 0x12000
	s_add_i32 s52, s38, 0x1a000
	s_add_i32 s53, s38, 0x14000
	s_add_i32 s54, s38, 0x1c000
	s_add_i32 s55, s38, 0x16000
	s_add_i32 s58, s38, 0x1e000
	s_or_b32 s24, s24, s62
	s_add_u32 s62, s10, s24
	s_addc_u32 s63, s11, s25
	s_add_i32 s24, s64, s65
	s_ashr_i32 s25, s24, 31
	s_lshl_b64 s[24:25], s[24:25], 20
	s_lshl_b64 s[64:65], s[22:23], 1
	s_add_u32 s23, s24, s64
	s_waitcnt vmcnt(0)
	s_addc_u32 s24, s25, s65
	v_and_b32_e32 v145, 0xffffc000, v3
	s_add_u32 s23, s10, s23
	v_mov_b32_e32 v8, 0
	s_mov_b32 s26, 1
	v_bitop3_b32 v142, v4, v1, v2 bitop3:0x36
	v_or_b32_e32 v149, 0x800, v145
	v_or_b32_e32 v150, 0x1000, v145
	v_or_b32_e32 v151, 0x1800, v145
	v_or_b32_e32 v152, 0x2000, v145
	v_or_b32_e32 v153, 0x2800, v145
	v_or_b32_e32 v154, 0x3000, v145
	v_or_b32_e32 v155, 0x3800, v145
	v_bitop3_b32 v156, v5, s33, v1 bitop3:0xde
	s_addc_u32 s64, s11, s24
	s_mov_b64 s[24:25], 0
	v_add_u32_e32 v158, v0, v143
	v_mov_b32_e32 v9, v8
	v_mov_b32_e32 v10, v8
	v_mov_b32_e32 v11, v8
	v_mov_b32_e32 v72, v8
	v_mov_b32_e32 v73, v8
	v_mov_b32_e32 v74, v8
	v_mov_b32_e32 v75, v8
	v_mov_b32_e32 v12, v8
	v_mov_b32_e32 v13, v8
	v_mov_b32_e32 v14, v8
	v_mov_b32_e32 v15, v8
	v_mov_b32_e32 v76, v8
	v_mov_b32_e32 v77, v8
	v_mov_b32_e32 v78, v8
	v_mov_b32_e32 v79, v8
	v_mov_b32_e32 v16, v8
	v_mov_b32_e32 v17, v8
	v_mov_b32_e32 v18, v8
	v_mov_b32_e32 v19, v8
	v_mov_b32_e32 v80, v8
	v_mov_b32_e32 v81, v8
	v_mov_b32_e32 v82, v8
	v_mov_b32_e32 v83, v8
	v_mov_b32_e32 v20, v8
	v_mov_b32_e32 v21, v8
	v_mov_b32_e32 v22, v8
	v_mov_b32_e32 v23, v8
	v_mov_b32_e32 v84, v8
	v_mov_b32_e32 v85, v8
	v_mov_b32_e32 v86, v8
	v_mov_b32_e32 v87, v8
	v_mov_b32_e32 v24, v8
	v_mov_b32_e32 v25, v8
	v_mov_b32_e32 v26, v8
	v_mov_b32_e32 v27, v8
	v_mov_b32_e32 v96, v8
	v_mov_b32_e32 v97, v8
	v_mov_b32_e32 v98, v8
	v_mov_b32_e32 v99, v8
	v_mov_b32_e32 v28, v8
	v_mov_b32_e32 v29, v8
	v_mov_b32_e32 v30, v8
	v_mov_b32_e32 v31, v8
	v_mov_b32_e32 v100, v8
	v_mov_b32_e32 v101, v8
	v_mov_b32_e32 v102, v8
	v_mov_b32_e32 v103, v8
	v_mov_b32_e32 v32, v8
	v_mov_b32_e32 v33, v8
	v_mov_b32_e32 v34, v8
	v_mov_b32_e32 v35, v8
	v_mov_b32_e32 v104, v8
	v_mov_b32_e32 v105, v8
	v_mov_b32_e32 v106, v8
	v_mov_b32_e32 v107, v8
	v_mov_b32_e32 v36, v8
	v_mov_b32_e32 v37, v8
	v_mov_b32_e32 v38, v8
	v_mov_b32_e32 v39, v8
	v_mov_b32_e32 v108, v8
	v_mov_b32_e32 v109, v8
	v_mov_b32_e32 v110, v8
	v_mov_b32_e32 v111, v8
	v_mov_b32_e32 v40, v8
	v_mov_b32_e32 v41, v8
	v_mov_b32_e32 v42, v8
	v_mov_b32_e32 v43, v8
	v_mov_b32_e32 v112, v8
	v_mov_b32_e32 v113, v8
	v_mov_b32_e32 v114, v8
	v_mov_b32_e32 v115, v8
	v_mov_b32_e32 v44, v8
	v_mov_b32_e32 v45, v8
	v_mov_b32_e32 v46, v8
	v_mov_b32_e32 v47, v8
	v_mov_b32_e32 v116, v8
	v_mov_b32_e32 v117, v8
	v_mov_b32_e32 v118, v8
	v_mov_b32_e32 v119, v8
	v_mov_b32_e32 v48, v8
	v_mov_b32_e32 v49, v8
	v_mov_b32_e32 v50, v8
	v_mov_b32_e32 v51, v8
	v_mov_b32_e32 v120, v8
	v_mov_b32_e32 v121, v8
	v_mov_b32_e32 v122, v8
	v_mov_b32_e32 v123, v8
	v_mov_b32_e32 v52, v8
	v_mov_b32_e32 v53, v8
	v_mov_b32_e32 v54, v8
	v_mov_b32_e32 v55, v8
	v_mov_b32_e32 v124, v8
	v_mov_b32_e32 v125, v8
	v_mov_b32_e32 v126, v8
	v_mov_b32_e32 v127, v8
	v_mov_b32_e32 v56, v8
	v_mov_b32_e32 v57, v8
	v_mov_b32_e32 v58, v8
	v_mov_b32_e32 v59, v8
	v_mov_b32_e32 v128, v8
	v_mov_b32_e32 v129, v8
	v_mov_b32_e32 v130, v8
	v_mov_b32_e32 v131, v8
	v_mov_b32_e32 v60, v8
	v_mov_b32_e32 v61, v8
	v_mov_b32_e32 v62, v8
	v_mov_b32_e32 v63, v8
	v_mov_b32_e32 v132, v8
	v_mov_b32_e32 v133, v8
	v_mov_b32_e32 v134, v8
	v_mov_b32_e32 v135, v8
	v_mov_b32_e32 v64, v8
	v_mov_b32_e32 v65, v8
	v_mov_b32_e32 v66, v8
	v_mov_b32_e32 v67, v8
	v_mov_b32_e32 v0, v8
	v_mov_b32_e32 v1, v8
	v_mov_b32_e32 v2, v8
	v_mov_b32_e32 v3, v8
	v_mov_b32_e32 v68, v8
	v_mov_b32_e32 v69, v8
	v_mov_b32_e32 v70, v8
	v_mov_b32_e32 v71, v8
	v_mov_b32_e32 v4, v8
	v_mov_b32_e32 v5, v8
	v_mov_b32_e32 v6, v8
	v_mov_b32_e32 v7, v8
	s_barrier
	s_add_u32 s65, s23, s24
	s_addc_u32 s72, s64, s25
	s_add_u32 s68, s65, 0x21ac0080
	s_addc_u32 s69, s72, 0
	s_add_u32 s73, s62, s24
	s_addc_u32 s74, s63, s25
	s_add_u32 s70, s73, 0x2000080
	s_addc_u32 s71, s74, 0
	v_add_u32_e32 v159, v142, v143
	v_add_u32_e32 v189, v142, v145
	ds_read_b128 v[160:163], v159 offset:32768
	ds_read_b128 v[164:167], v189
	ds_read_b128 v[168:171], v159 offset:34816
	ds_read_b128 v[172:175], v189 offset:2048
	ds_read_b128 v[176:179], v159 offset:36864
	ds_read_b128 v[180:183], v159 offset:38912
	ds_read_b128 v[214:217], v189 offset:4096
	ds_read_b128 v[218:221], v189 offset:6144
	s_branch .Lmy_rot_758
.LBB0_758:
	s_add_u32 s65, s23, s24
	s_addc_u32 s72, s64, s25
	s_add_u32 s68, s65, 0x21ac0080
	s_addc_u32 s69, s72, 0
	s_add_u32 s73, s62, s24
	s_addc_u32 s74, s63, s25
	s_add_u32 s70, s73, 0x2000080
	s_addc_u32 s71, s74, 0
	v_add_u32_e32 v159, v142, v143
	v_add_u32_e32 v189, v142, v145
	ds_read_b128 v[160:163], v159 offset:32768
	ds_read_b128 v[164:167], v189
	v_mfma_f32_16x16x32_bf16 v[76:79], v[168:171], v[214:217], v[76:79]
	v_mfma_f32_16x16x32_bf16 v[64:67], v[168:171], v[218:221], v[64:67]
	ds_read_b128 v[168:171], v159 offset:34816
	v_mfma_f32_16x16x32_bf16 v[12:15], v[172:175], v[214:217], v[12:15]
	v_mfma_f32_16x16x32_bf16 v[0:3], v[172:175], v[218:221], v[0:3]
	ds_read_b128 v[172:175], v189 offset:2048
	v_mfma_f32_16x16x32_bf16 v[72:75], v[176:179], v[214:217], v[72:75]
	v_mfma_f32_16x16x32_bf16 v[68:71], v[176:179], v[218:221], v[68:71]
	ds_read_b128 v[176:179], v159 offset:36864
	v_mfma_f32_16x16x32_bf16 v[8:11], v[180:183], v[214:217], v[8:11]
	v_mfma_f32_16x16x32_bf16 v[4:7], v[180:183], v[218:221], v[4:7]
	ds_read_b128 v[180:183], v159 offset:38912
	ds_read_b128 v[214:217], v189 offset:4096
	ds_read_b128 v[218:221], v189 offset:6144
.Lmy_rot_758:
	s_waitcnt lgkmcnt(6)
	v_mfma_f32_16x16x32_bf16 v[132:135], v[160:163], v[164:167], v[132:135]
	s_waitcnt lgkmcnt(5)
	v_mfma_f32_16x16x32_bf16 v[60:63], v[168:171], v[164:167], v[60:63]
	s_waitcnt lgkmcnt(4)
	s_mov_b32 m0, s49
	v_mfma_f32_16x16x32_bf16 v[124:127], v[160:163], v[172:175], v[124:127]
	global_load_lds_dwordx4 v88, s[68:69]
	v_mfma_f32_16x16x32_bf16 v[52:55], v[168:171], v[172:175], v[52:55]
	s_waitcnt lgkmcnt(3)
	v_mfma_f32_16x16x32_bf16 v[128:131], v[176:179], v[164:167], v[128:131]
	v_mfma_f32_16x16x32_bf16 v[120:123], v[176:179], v[172:175], v[120:123]
	s_waitcnt lgkmcnt(2)
	s_mov_b32 m0, s50
	v_mfma_f32_16x16x32_bf16 v[56:59], v[180:183], v[164:167], v[56:59]
	global_load_lds_dwordx4 v90, s[70:71]
	ds_read_b128 v[164:167], v189 offset:8192
	v_mfma_f32_16x16x32_bf16 v[48:51], v[180:183], v[172:175], v[48:51]
	ds_read_b128 v[172:175], v189 offset:10240
	s_waitcnt lgkmcnt(3)
	v_mfma_f32_16x16x32_bf16 v[116:119], v[160:163], v[214:217], v[116:119]
	v_mfma_f32_16x16x32_bf16 v[44:47], v[168:171], v[214:217], v[44:47]
	s_mov_b32 m0, s51
	v_mfma_f32_16x16x32_bf16 v[112:115], v[176:179], v[214:217], v[112:115]
	global_load_lds_dwordx4 v92, s[68:69]
	v_mfma_f32_16x16x32_bf16 v[40:43], v[180:183], v[214:217], v[40:43]
	ds_read_b128 v[214:217], v189 offset:12288
	s_waitcnt lgkmcnt(3)
	v_mfma_f32_16x16x32_bf16 v[108:111], v[160:163], v[218:221], v[108:111]
	v_mfma_f32_16x16x32_bf16 v[36:39], v[168:171], v[218:221], v[36:39]
	s_mov_b32 m0, s52
	v_mfma_f32_16x16x32_bf16 v[104:107], v[176:179], v[218:221], v[104:107]
	global_load_lds_dwordx4 v94, s[70:71]
	v_mfma_f32_16x16x32_bf16 v[32:35], v[180:183], v[218:221], v[32:35]
	ds_read_b128 v[218:221], v189 offset:14336
	s_waitcnt lgkmcnt(3)
	v_mfma_f32_16x16x32_bf16 v[28:31], v[168:171], v[164:167], v[28:31]
	s_waitcnt lgkmcnt(2)
	v_mfma_f32_16x16x32_bf16 v[20:23], v[168:171], v[172:175], v[20:23]
	s_waitcnt lgkmcnt(1)
	s_mov_b32 m0, s53
	v_mfma_f32_16x16x32_bf16 v[12:15], v[168:171], v[214:217], v[12:15]
	global_load_lds_dwordx4 v136, s[68:69]
	s_waitcnt lgkmcnt(0)
	v_mfma_f32_16x16x32_bf16 v[0:3], v[168:171], v[218:221], v[0:3]
	ds_read_b128 v[168:171], v159 offset:33792
	v_mfma_f32_16x16x32_bf16 v[100:103], v[160:163], v[164:167], v[100:103]
	v_mfma_f32_16x16x32_bf16 v[84:87], v[160:163], v[172:175], v[84:87]
	s_mov_b32 m0, s54
	v_mfma_f32_16x16x32_bf16 v[76:79], v[160:163], v[214:217], v[76:79]
	global_load_lds_dwordx4 v138, s[70:71]
	v_mfma_f32_16x16x32_bf16 v[64:67], v[160:163], v[218:221], v[64:67]
	ds_read_b128 v[160:163], v189 offset:1024
	v_mfma_f32_16x16x32_bf16 v[80:83], v[176:179], v[172:175], v[80:83]
	v_mfma_f32_16x16x32_bf16 v[16:19], v[180:183], v[172:175], v[16:19]
	ds_read_b128 v[172:175], v159 offset:35840
	s_mov_b32 m0, s55
	v_mfma_f32_16x16x32_bf16 v[96:99], v[176:179], v[164:167], v[96:99]
	global_load_lds_dwordx4 v140, s[68:69]
	v_mfma_f32_16x16x32_bf16 v[24:27], v[180:183], v[164:167], v[24:27]
	ds_read_b128 v[164:167], v189 offset:3072
	v_mfma_f32_16x16x32_bf16 v[72:75], v[176:179], v[214:217], v[72:75]
	v_mfma_f32_16x16x32_bf16 v[8:11], v[180:183], v[214:217], v[8:11]
	ds_read_b128 v[214:217], v189 offset:5120
	s_mov_b32 m0, s58
	v_mfma_f32_16x16x32_bf16 v[68:71], v[176:179], v[218:221], v[68:71]
	global_load_lds_dwordx4 v146, s[70:71]
	ds_read_b128 v[176:179], v159 offset:37888
	v_mfma_f32_16x16x32_bf16 v[4:7], v[180:183], v[218:221], v[4:7]
	ds_read_b128 v[180:183], v159 offset:39936
	ds_read_b128 v[218:221], v189 offset:7168
	s_waitcnt lgkmcnt(6)
	v_mfma_f32_16x16x32_bf16 v[132:135], v[168:171], v[160:163], v[132:135]
	s_waitcnt lgkmcnt(5)
	v_mfma_f32_16x16x32_bf16 v[60:63], v[172:175], v[160:163], v[60:63]
	s_waitcnt lgkmcnt(4)
	v_mfma_f32_16x16x32_bf16 v[124:127], v[168:171], v[164:167], v[124:127]
	v_mfma_f32_16x16x32_bf16 v[52:55], v[172:175], v[164:167], v[52:55]
	s_waitcnt lgkmcnt(3)
	v_mfma_f32_16x16x32_bf16 v[116:119], v[168:171], v[214:217], v[116:119]
	v_mfma_f32_16x16x32_bf16 v[44:47], v[172:175], v[214:217], v[44:47]
	s_waitcnt lgkmcnt(2)
	v_mfma_f32_16x16x32_bf16 v[128:131], v[176:179], v[160:163], v[128:131]
	s_waitcnt lgkmcnt(1)
	v_mfma_f32_16x16x32_bf16 v[56:59], v[180:183], v[160:163], v[56:59]
	ds_read_b128 v[160:163], v189 offset:9216
	v_mfma_f32_16x16x32_bf16 v[120:123], v[176:179], v[164:167], v[120:123]
	v_mfma_f32_16x16x32_bf16 v[48:51], v[180:183], v[164:167], v[48:51]
	ds_read_b128 v[164:167], v189 offset:11264
	v_mfma_f32_16x16x32_bf16 v[112:115], v[176:179], v[214:217], v[112:115]
	v_mfma_f32_16x16x32_bf16 v[40:43], v[180:183], v[214:217], v[40:43]
	ds_read_b128 v[214:217], v189 offset:13312
	s_waitcnt lgkmcnt(3)
	v_mfma_f32_16x16x32_bf16 v[108:111], v[168:171], v[218:221], v[108:111]
	v_mfma_f32_16x16x32_bf16 v[36:39], v[172:175], v[218:221], v[36:39]
	v_mfma_f32_16x16x32_bf16 v[104:107], v[176:179], v[218:221], v[104:107]
	v_mfma_f32_16x16x32_bf16 v[32:35], v[180:183], v[218:221], v[32:35]
	ds_read_b128 v[218:221], v189 offset:15360
	s_waitcnt lgkmcnt(3)
	v_mfma_f32_16x16x32_bf16 v[100:103], v[168:171], v[160:163], v[100:103]
	v_mfma_f32_16x16x32_bf16 v[28:31], v[172:175], v[160:163], v[28:31]
	v_mfma_f32_16x16x32_bf16 v[96:99], v[176:179], v[160:163], v[96:99]
	v_mfma_f32_16x16x32_bf16 v[24:27], v[180:183], v[160:163], v[24:27]
	s_waitcnt lgkmcnt(2)
	v_mfma_f32_16x16x32_bf16 v[84:87], v[168:171], v[164:167], v[84:87]
	v_mfma_f32_16x16x32_bf16 v[20:23], v[172:175], v[164:167], v[20:23]
	v_mfma_f32_16x16x32_bf16 v[80:83], v[176:179], v[164:167], v[80:83]
	v_mfma_f32_16x16x32_bf16 v[16:19], v[180:183], v[164:167], v[16:19]
	s_add_u32 s65, s65, 0x21ac0100
	s_addc_u32 s68, s72, 0
	s_add_u32 s70, s73, 0x2000100
	s_addc_u32 s71, s74, 0
	s_cmp_lt_u32 s26, 3
	s_cselect_b32 s69, s68, s45
	s_cselect_b32 s68, s65, s27
	s_waitcnt vmcnt(0)
	s_waitcnt lgkmcnt(0)
	s_barrier
	s_cselect_b32 s71, s71, s47
	s_cselect_b32 s70, s70, s46
	ds_read_b128 v[160:163], v158
	v_add_u32_e32 v159, v156, v145
	ds_read_b128 v[164:167], v159
	v_mfma_f32_16x16x32_bf16 v[76:79], v[168:171], v[214:217], v[76:79]
	v_mfma_f32_16x16x32_bf16 v[64:67], v[168:171], v[218:221], v[64:67]
	ds_read_b128 v[168:171], v158 offset:2048
	v_mfma_f32_16x16x32_bf16 v[12:15], v[172:175], v[214:217], v[12:15]
	v_mfma_f32_16x16x32_bf16 v[0:3], v[172:175], v[218:221], v[0:3]
	v_add_u32_e32 v159, v156, v149
	ds_read_b128 v[172:175], v159
	v_mfma_f32_16x16x32_bf16 v[72:75], v[176:179], v[214:217], v[72:75]
	v_mfma_f32_16x16x32_bf16 v[68:71], v[176:179], v[218:221], v[68:71]
	ds_read_b128 v[176:179], v158 offset:4096
	v_mfma_f32_16x16x32_bf16 v[8:11], v[180:183], v[214:217], v[8:11]
	v_mfma_f32_16x16x32_bf16 v[4:7], v[180:183], v[218:221], v[4:7]
	ds_read_b128 v[180:183], v158 offset:6144
	v_add_u32_e32 v159, v156, v150
	ds_read_b128 v[214:217], v159
	v_add_u32_e32 v159, v156, v151
	ds_read_b128 v[218:221], v159
	s_waitcnt lgkmcnt(6)
	v_mfma_f32_16x16x32_bf16 v[132:135], v[160:163], v[164:167], v[132:135]
	s_waitcnt lgkmcnt(5)
	v_mfma_f32_16x16x32_bf16 v[60:63], v[168:171], v[164:167], v[60:63]
	s_waitcnt lgkmcnt(4)
	s_mov_b32 m0, s38
	v_mfma_f32_16x16x32_bf16 v[124:127], v[160:163], v[172:175], v[124:127]
	global_load_lds_dwordx4 v88, s[68:69]
	v_mfma_f32_16x16x32_bf16 v[52:55], v[168:171], v[172:175], v[52:55]
	s_waitcnt lgkmcnt(3)
	v_mfma_f32_16x16x32_bf16 v[128:131], v[176:179], v[164:167], v[128:131]
	v_mfma_f32_16x16x32_bf16 v[120:123], v[176:179], v[172:175], v[120:123]
	s_waitcnt lgkmcnt(2)
	s_mov_b32 m0, s1
	v_mfma_f32_16x16x32_bf16 v[56:59], v[180:183], v[164:167], v[56:59]
	global_load_lds_dwordx4 v90, s[70:71]
	v_add_u32_e32 v159, v156, v152
	ds_read_b128 v[164:167], v159
	v_mfma_f32_16x16x32_bf16 v[48:51], v[180:183], v[172:175], v[48:51]
	v_add_u32_e32 v159, v156, v153
	ds_read_b128 v[172:175], v159
	s_waitcnt lgkmcnt(3)
	v_mfma_f32_16x16x32_bf16 v[116:119], v[160:163], v[214:217], v[116:119]
	v_mfma_f32_16x16x32_bf16 v[44:47], v[168:171], v[214:217], v[44:47]
	s_mov_b32 m0, s39
	v_mfma_f32_16x16x32_bf16 v[112:115], v[176:179], v[214:217], v[112:115]
	global_load_lds_dwordx4 v92, s[68:69]
	v_mfma_f32_16x16x32_bf16 v[40:43], v[180:183], v[214:217], v[40:43]
	v_add_u32_e32 v159, v156, v154
	ds_read_b128 v[214:217], v159
	s_waitcnt lgkmcnt(3)
	v_mfma_f32_16x16x32_bf16 v[108:111], v[160:163], v[218:221], v[108:111]
	v_mfma_f32_16x16x32_bf16 v[36:39], v[168:171], v[218:221], v[36:39]
	s_mov_b32 m0, s40
	v_mfma_f32_16x16x32_bf16 v[104:107], v[176:179], v[218:221], v[104:107]
	global_load_lds_dwordx4 v94, s[70:71]
	v_mfma_f32_16x16x32_bf16 v[32:35], v[180:183], v[218:221], v[32:35]
	v_add_u32_e32 v159, v156, v155
	ds_read_b128 v[218:221], v159
	s_waitcnt lgkmcnt(3)
	v_mfma_f32_16x16x32_bf16 v[28:31], v[168:171], v[164:167], v[28:31]
	s_waitcnt lgkmcnt(2)
	v_mfma_f32_16x16x32_bf16 v[20:23], v[168:171], v[172:175], v[20:23]
	s_waitcnt lgkmcnt(1)
	s_mov_b32 m0, s41
	v_mfma_f32_16x16x32_bf16 v[12:15], v[168:171], v[214:217], v[12:15]
	global_load_lds_dwordx4 v136, s[68:69]
	s_waitcnt lgkmcnt(0)
	v_mfma_f32_16x16x32_bf16 v[0:3], v[168:171], v[218:221], v[0:3]
	ds_read_b128 v[168:171], v158 offset:1024
	v_mfma_f32_16x16x32_bf16 v[100:103], v[160:163], v[164:167], v[100:103]
	v_mfma_f32_16x16x32_bf16 v[84:87], v[160:163], v[172:175], v[84:87]
	s_mov_b32 m0, s42
	v_mfma_f32_16x16x32_bf16 v[76:79], v[160:163], v[214:217], v[76:79]
	global_load_lds_dwordx4 v138, s[70:71]
	v_mfma_f32_16x16x32_bf16 v[64:67], v[160:163], v[218:221], v[64:67]
	v_add_u32_e32 v159, v157, v145
	ds_read_b128 v[160:163], v159
	v_mfma_f32_16x16x32_bf16 v[80:83], v[176:179], v[172:175], v[80:83]
	v_mfma_f32_16x16x32_bf16 v[16:19], v[180:183], v[172:175], v[16:19]
	ds_read_b128 v[172:175], v158 offset:3072
	s_mov_b32 m0, s43
	v_mfma_f32_16x16x32_bf16 v[96:99], v[176:179], v[164:167], v[96:99]
	global_load_lds_dwordx4 v140, s[68:69]
	v_mfma_f32_16x16x32_bf16 v[24:27], v[180:183], v[164:167], v[24:27]
	v_add_u32_e32 v159, v157, v149
	ds_read_b128 v[164:167], v159
	v_mfma_f32_16x16x32_bf16 v[72:75], v[176:179], v[214:217], v[72:75]
	v_mfma_f32_16x16x32_bf16 v[8:11], v[180:183], v[214:217], v[8:11]
	v_add_u32_e32 v159, v157, v150
	ds_read_b128 v[214:217], v159
	s_mov_b32 m0, s44
	v_mfma_f32_16x16x32_bf16 v[68:71], v[176:179], v[218:221], v[68:71]
	global_load_lds_dwordx4 v146, s[70:71]
	ds_read_b128 v[176:179], v158 offset:5120
	v_mfma_f32_16x16x32_bf16 v[4:7], v[180:183], v[218:221], v[4:7]
	ds_read_b128 v[180:183], v158 offset:7168
	v_add_u32_e32 v159, v157, v151
	ds_read_b128 v[218:221], v159
	s_waitcnt lgkmcnt(6)
	v_mfma_f32_16x16x32_bf16 v[132:135], v[168:171], v[160:163], v[132:135]
	s_waitcnt lgkmcnt(5)
	v_mfma_f32_16x16x32_bf16 v[60:63], v[172:175], v[160:163], v[60:63]
	s_waitcnt lgkmcnt(4)
	v_mfma_f32_16x16x32_bf16 v[124:127], v[168:171], v[164:167], v[124:127]
	v_mfma_f32_16x16x32_bf16 v[52:55], v[172:175], v[164:167], v[52:55]
	s_waitcnt lgkmcnt(3)
	v_mfma_f32_16x16x32_bf16 v[116:119], v[168:171], v[214:217], v[116:119]
	v_mfma_f32_16x16x32_bf16 v[44:47], v[172:175], v[214:217], v[44:47]
	s_waitcnt lgkmcnt(2)
	v_mfma_f32_16x16x32_bf16 v[128:131], v[176:179], v[160:163], v[128:131]
	s_waitcnt lgkmcnt(1)
	v_mfma_f32_16x16x32_bf16 v[56:59], v[180:183], v[160:163], v[56:59]
	v_add_u32_e32 v159, v157, v152
	ds_read_b128 v[160:163], v159
	v_mfma_f32_16x16x32_bf16 v[120:123], v[176:179], v[164:167], v[120:123]
	v_mfma_f32_16x16x32_bf16 v[48:51], v[180:183], v[164:167], v[48:51]
	v_add_u32_e32 v159, v157, v153
	ds_read_b128 v[164:167], v159
	v_mfma_f32_16x16x32_bf16 v[112:115], v[176:179], v[214:217], v[112:115]
	v_mfma_f32_16x16x32_bf16 v[40:43], v[180:183], v[214:217], v[40:43]
	v_add_u32_e32 v159, v157, v154
	ds_read_b128 v[214:217], v159
	s_waitcnt lgkmcnt(3)
	v_mfma_f32_16x16x32_bf16 v[108:111], v[168:171], v[218:221], v[108:111]
	v_mfma_f32_16x16x32_bf16 v[36:39], v[172:175], v[218:221], v[36:39]
	v_mfma_f32_16x16x32_bf16 v[104:107], v[176:179], v[218:221], v[104:107]
	v_mfma_f32_16x16x32_bf16 v[32:35], v[180:183], v[218:221], v[32:35]
	v_add_u32_e32 v159, v157, v155
	ds_read_b128 v[218:221], v159
	s_waitcnt lgkmcnt(3)
	v_mfma_f32_16x16x32_bf16 v[100:103], v[168:171], v[160:163], v[100:103]
	v_mfma_f32_16x16x32_bf16 v[28:31], v[172:175], v[160:163], v[28:31]
	v_mfma_f32_16x16x32_bf16 v[96:99], v[176:179], v[160:163], v[96:99]
	v_mfma_f32_16x16x32_bf16 v[24:27], v[180:183], v[160:163], v[24:27]
	s_waitcnt lgkmcnt(2)
	v_mfma_f32_16x16x32_bf16 v[84:87], v[168:171], v[164:167], v[84:87]
	v_mfma_f32_16x16x32_bf16 v[20:23], v[172:175], v[164:167], v[20:23]
	v_mfma_f32_16x16x32_bf16 v[80:83], v[176:179], v[164:167], v[80:83]
	v_mfma_f32_16x16x32_bf16 v[16:19], v[180:183], v[164:167], v[16:19]
	s_waitcnt vmcnt(0)
	s_add_u32 s24, s24, 0x100
	s_addc_u32 s25, s25, 0
	s_add_i32 s26, s26, 2
	s_cmpk_lg_i32 s24, 0x200
	s_waitcnt lgkmcnt(0)
	s_barrier
	s_cbranch_scc1 .LBB0_758
	v_mfma_f32_16x16x32_bf16 v[76:79], v[168:171], v[214:217], v[76:79]
	v_mfma_f32_16x16x32_bf16 v[64:67], v[168:171], v[218:221], v[64:67]
	v_mfma_f32_16x16x32_bf16 v[12:15], v[172:175], v[214:217], v[12:15]
	v_mfma_f32_16x16x32_bf16 v[0:3], v[172:175], v[218:221], v[0:3]
	v_mfma_f32_16x16x32_bf16 v[72:75], v[176:179], v[214:217], v[72:75]
	v_mfma_f32_16x16x32_bf16 v[68:71], v[176:179], v[218:221], v[68:71]
	v_mfma_f32_16x16x32_bf16 v[8:11], v[180:183], v[214:217], v[8:11]
	v_mfma_f32_16x16x32_bf16 v[4:7], v[180:183], v[218:221], v[4:7]
	s_nop 15
	s_nop 15
	v_mov_b32_e32 v88, v184
	s_lshl_b32 s0, s0, 8
	v_lshrrev_b32_e32 v89, 1, v88
	v_and_b32_e32 v89, 0x60, v89
	v_lshl_or_b32 v89, s37, 7, v89
	v_or_b32_e32 v142, s22, v89
	v_lshrrev_b32_e32 v89, 2, v88
	v_and_b32_e32 v146, 12, v89
	v_ashrrev_i32_e32 v89, 1, v88
	v_and_b32_e32 v89, 0xffffff80, v89
	v_and_or_b32 v88, v88, 15, s0
	v_add_u32_e32 v172, v88, v89
	v_or_b32_e32 v182, v142, v146
	v_ashrrev_i32_e32 v173, 31, v172
	v_ashrrev_i32_e32 v183, 31, v182
	v_lshlrev_b64 v[88:89], 12, v[172:173]
	v_lshlrev_b64 v[92:93], 2, v[182:183]
	v_lshl_add_u64 v[140:141], s[2:3], 0, v[88:89]
	v_lshl_add_u64 v[88:89], s[4:5], 0, v[92:93]
	global_load_dwordx4 v[136:139], v[88:89], off
	s_mov_b32 s24, 0xbfb8aa3b
	s_mov_b32 s25, 0x42ce8ed0
	s_mov_b32 s26, 0xc2b17218
	s_mov_b32 s37, 0x3f2aaaab
	s_mov_b32 s38, 0x3f317218
	v_lshl_add_u64 v[88:89], s[6:7], 0, v[92:93]
	v_lshl_add_u64 v[92:93], s[8:9], 0, v[92:93]
	global_load_dwordx4 v[92:95], v[92:93], off
	s_mov_b32 s27, 0x7f800000
	global_load_dwordx4 v[88:91], v[88:89], off
	s_mov_b32 s39, 0x33800000
	s_mov_b32 s40, 0xbd4ccccd
	s_mov_b32 s44, 0xc1000000
	s_waitcnt vmcnt(2)
	v_mul_f32_e32 v143, 0xbfb8aa3b, v136
	v_fma_f32 v145, v136, s24, -v143
	v_rndne_f32_e32 v149, v143
	v_fmac_f32_e32 v145, 0xb2a5705f, v136
	v_sub_f32_e32 v143, v143, v149
	v_add_f32_e32 v143, v143, v145
	v_exp_f32_e32 v143, v143
	v_cvt_i32_f32_e32 v145, v149
	v_cmp_nlt_f32_e32 vcc, s25, v136
	s_waitcnt vmcnt(1)
	v_add_f32_e32 v128, v128, v92
	v_mul_f32_e32 v128, 0xbfb8aa3b, v128
	v_ldexp_f32 v143, v143, v145
	v_cndmask_b32_e32 v143, 0, v143, vcc
	v_cmp_ngt_f32_e32 vcc, s26, v136
	v_exp_f32_e32 v128, v128
	v_add_f32_e32 v112, v112, v92
	v_cndmask_b32_e32 v143, v209, v143, vcc
	v_add_f32_e32 v136, 1.0, v143
	v_add_f32_e32 v145, -1.0, v136
	v_sub_f32_e32 v149, v145, v136
	v_add_f32_e32 v149, 1.0, v149
	v_sub_f32_e32 v145, v143, v145
	v_add_f32_e32 v145, v145, v149
	v_frexp_mant_f32_e32 v149, v136
	v_cvt_f64_f32_e32 v[150:151], v136
	v_cmp_gt_f32_e32 vcc, s37, v149
	v_frexp_exp_i32_f64_e32 v149, v[150:151]
	v_add_f32_e32 v128, 1.0, v128
	v_subbrev_co_u32_e32 v158, vcc, 0, v149, vcc
	v_sub_u32_e32 v149, 0, v158
	v_ldexp_f32 v136, v136, v149
	v_ldexp_f32 v145, v145, v149
	v_add_f32_e32 v149, -1.0, v136
	v_add_f32_e32 v150, 1.0, v149
	v_sub_f32_e32 v150, v136, v150
	v_add_f32_e32 v150, v145, v150
	v_add_f32_e32 v151, v149, v150
	v_sub_f32_e32 v149, v149, v151
	v_add_f32_e32 v149, v150, v149
	v_add_f32_e32 v150, 1.0, v136
	v_add_f32_e32 v152, -1.0, v150
	v_sub_f32_e32 v136, v136, v152
	v_add_f32_e32 v136, v145, v136
	v_add_f32_e32 v145, v150, v136
	v_rcp_f32_e32 v159, v145
	v_sub_f32_e32 v150, v150, v145
	v_add_f32_e32 v136, v136, v150
	v_cmp_nlt_f32_e32 vcc, s25, v137
	v_mul_f32_e32 v160, v151, v159
	v_mul_f32_e32 v152, v145, v160
	v_fma_f32 v154, v160, v145, -v152
	v_fmac_f32_e32 v154, v160, v136
	v_add_f32_e32 v150, v152, v154
	v_sub_f32_e32 v153, v151, v150
	v_pk_add_f32 v[156:157], v[150:151], v[152:153] neg_lo:[0,1] neg_hi:[0,1]
	v_mov_b32_e32 v155, v150
	v_pk_add_f32 v[150:151], v[156:157], v[154:155] neg_lo:[0,1] neg_hi:[0,1]
	v_mul_f32_e32 v112, 0xbfb8aa3b, v112
	v_add_f32_e32 v149, v149, v151
	v_add_f32_e32 v149, v150, v149
	v_add_f32_e32 v151, v153, v149
	v_mul_f32_e32 v161, v159, v151
	v_mul_f32_e32 v152, v145, v161
	v_fma_f32 v154, v161, v145, -v152
	v_fmac_f32_e32 v154, v161, v136
	v_add_f32_e32 v150, v152, v154
	v_sub_f32_e32 v136, v153, v151
	v_sub_f32_e32 v153, v151, v150
	v_pk_add_f32 v[156:157], v[150:151], v[152:153] neg_lo:[0,1] neg_hi:[0,1]
	v_mov_b32_e32 v155, v150
	v_add_f32_e32 v136, v149, v136
	v_pk_add_f32 v[150:151], v[156:157], v[154:155] neg_lo:[0,1] neg_hi:[0,1]
	v_add_f32_e32 v145, v160, v161
	v_add_f32_e32 v136, v136, v151
	v_add_f32_e32 v136, v150, v136
	v_add_f32_e32 v136, v153, v136
	v_sub_f32_e32 v149, v145, v160
	v_mul_f32_e32 v136, v159, v136
	v_sub_f32_e32 v149, v161, v149
	v_add_f32_e32 v136, v149, v136
	v_add_f32_e32 v151, v145, v136
	v_cvt_f32_i32_e32 v150, v158
	v_mul_f32_e32 v152, v151, v151
	v_fmamk_f32 v149, v152, 0x3e9b6dac, v195
	v_fmaak_f32 v149, v152, v149, 0x3f2aaada
	v_sub_f32_e32 v145, v151, v145
	v_ldexp_f32 v153, v151, 1
	v_mul_f32_e32 v151, v151, v152
	v_pk_mul_f32 v[154:155], v[150:151], v[148:149]
	v_sub_f32_e32 v136, v136, v145
	v_fma_f32 v152, v150, s38, -v154
	v_fmac_f32_e32 v152, 0xb102e308, v150
	v_pk_add_f32 v[156:157], v[154:155], v[152:153]
	v_ldexp_f32 v136, v136, 1
	v_sub_f32_e32 v145, v157, v153
	v_sub_f32_e32 v145, v155, v145
	v_add_f32_e32 v159, v136, v145
	v_mul_f32_e32 v136, 0xbfb8aa3b, v137
	v_fma_f32 v145, v137, s24, -v136
	v_rndne_f32_e32 v149, v136
	v_fmac_f32_e32 v145, 0xb2a5705f, v137
	v_sub_f32_e32 v136, v136, v149
	v_add_f32_e32 v136, v136, v145
	v_exp_f32_e32 v136, v136
	v_cvt_i32_f32_e32 v145, v149
	v_mov_b32_e32 v158, v154
	v_pk_add_f32 v[154:155], v[156:157], v[154:155] neg_lo:[0,1] neg_hi:[0,1]
	v_pk_add_f32 v[160:161], v[156:157], v[158:159]
	v_ldexp_f32 v136, v136, v145
	v_cndmask_b32_e32 v136, 0, v136, vcc
	v_cmp_ngt_f32_e32 vcc, s26, v137
	v_mov_b32_e32 v155, v161
	v_mov_b32_e32 v153, v156
	v_cndmask_b32_e32 v173, v209, v136, vcc
	v_add_f32_e32 v145, 1.0, v173
	v_add_f32_e32 v136, -1.0, v145
	v_sub_f32_e32 v137, v136, v145
	v_add_f32_e32 v137, 1.0, v137
	v_sub_f32_e32 v136, v173, v136
	v_pk_add_f32 v[150:151], v[152:153], v[154:155] neg_lo:[0,1] neg_hi:[0,1]
	v_pk_add_f32 v[152:153], v[152:153], v[154:155]
	v_add_f32_e32 v149, v136, v137
	v_frexp_mant_f32_e32 v136, v145
	v_pk_add_f32 v[154:155], v[152:153], v[156:157] op_sel:[1,0] op_sel_hi:[0,1] neg_lo:[0,1] neg_hi:[0,1]
	v_cmp_gt_f32_e32 vcc, s37, v136
	v_cvt_f64_f32_e32 v[136:137], v145
	v_pk_add_f32 v[162:163], v[160:161], v[154:155] op_sel_hi:[1,0] neg_lo:[0,1] neg_hi:[0,1]
	v_mov_b32_e32 v152, v161
	v_pk_mov_b32 v[154:155], v[156:157], v[154:155] op_sel:[1,0]
	v_frexp_exp_i32_f64_e32 v136, v[136:137]
	v_pk_add_f32 v[154:155], v[152:153], v[154:155] neg_lo:[0,1] neg_hi:[0,1]
	v_subbrev_co_u32_e32 v152, vcc, 0, v136, vcc
	v_sub_u32_e32 v136, 0, v152
	v_ldexp_f32 v145, v145, v136
	v_ldexp_f32 v136, v149, v136
	v_add_f32_e32 v149, -1.0, v145
	v_mov_b32_e32 v158, v159
	v_mov_b32_e32 v159, v156
	v_add_f32_e32 v137, 1.0, v149
	v_pk_add_f32 v[154:155], v[158:159], v[154:155] neg_lo:[0,1] neg_hi:[0,1]
	v_mov_b32_e32 v162, v150
	v_sub_f32_e32 v137, v145, v137
	v_pk_add_f32 v[156:157], v[162:163], v[154:155]
	v_add_f32_e32 v155, v136, v137
	v_add_f32_e32 v137, v149, v155
	v_sub_f32_e32 v149, v149, v137
	v_add_f32_e32 v149, v155, v149
	v_add_f32_e32 v155, 1.0, v145
	v_add_f32_e32 v158, -1.0, v155
	v_sub_f32_e32 v145, v145, v158
	v_add_f32_e32 v136, v136, v145
	v_add_f32_e32 v145, v155, v136
	v_rcp_f32_e32 v164, v145
	v_sub_f32_e32 v155, v155, v145
	v_add_f32_e32 v155, v136, v155
	v_cmp_nlt_f32_e32 vcc, s25, v138
	v_mul_f32_e32 v165, v137, v164
	v_mul_f32_e32 v158, v145, v165
	v_fma_f32 v160, v165, v145, -v158
	v_fmac_f32_e32 v160, v165, v155
	v_add_f32_e32 v136, v158, v160
	v_sub_f32_e32 v159, v137, v136
	v_pk_add_f32 v[162:163], v[136:137], v[158:159] neg_lo:[0,1] neg_hi:[0,1]
	v_mov_b32_e32 v161, v136
	v_pk_add_f32 v[136:137], v[162:163], v[160:161] neg_lo:[0,1] neg_hi:[0,1]
	v_exp_f32_e32 v112, v112
	v_add_f32_e32 v137, v149, v137
	v_add_f32_e32 v136, v136, v137
	v_add_f32_e32 v137, v159, v136
	v_mul_f32_e32 v149, v164, v137
	v_mul_f32_e32 v158, v145, v149
	v_fma_f32 v160, v149, v145, -v158
	v_fmac_f32_e32 v160, v149, v155
	v_sub_f32_e32 v145, v159, v137
	v_add_f32_e32 v145, v136, v145
	v_add_f32_e32 v136, v158, v160
	v_sub_f32_e32 v159, v137, v136
	v_pk_add_f32 v[162:163], v[136:137], v[158:159] neg_lo:[0,1] neg_hi:[0,1]
	v_mov_b32_e32 v161, v136
	v_pk_add_f32 v[136:137], v[162:163], v[160:161] neg_lo:[0,1] neg_hi:[0,1]
	v_add_f32_e32 v72, v72, v92
	v_add_f32_e32 v137, v145, v137
	v_add_f32_e32 v136, v136, v137
	v_add_f32_e32 v137, v165, v149
	v_add_f32_e32 v136, v159, v136
	v_sub_f32_e32 v145, v137, v165
	v_mul_f32_e32 v136, v164, v136
	v_sub_f32_e32 v145, v149, v145
	v_add_f32_e32 v145, v145, v136
	v_add_f32_e32 v155, v137, v145
	v_mul_f32_e32 v158, v155, v155
	v_fmamk_f32 v136, v158, 0x3e9b6dac, v195
	v_fmaak_f32 v149, v158, v136, 0x3f2aaada
	v_cvt_f32_i32_e32 v136, v152
	v_sub_f32_e32 v137, v155, v137
	v_sub_f32_e32 v137, v145, v137
	v_ldexp_f32 v145, v137, 1
	v_mul_f32_e32 v137, v155, v158
	v_pk_mul_f32 v[160:161], v[136:137], v[148:149]
	v_ldexp_f32 v159, v155, 1
	v_fma_f32 v158, v136, s38, -v160
	v_fmac_f32_e32 v158, 0xb102e308, v136
	v_pk_add_f32 v[136:137], v[160:161], v[158:159]
	v_mov_b32_e32 v162, v160
	v_sub_f32_e32 v149, v137, v159
	v_sub_f32_e32 v149, v161, v149
	v_add_f32_e32 v163, v145, v149
	v_pk_add_f32 v[160:161], v[136:137], v[160:161] neg_lo:[0,1] neg_hi:[0,1]
	v_pk_add_f32 v[164:165], v[136:137], v[162:163]
	v_mov_b32_e32 v159, v136
	v_mov_b32_e32 v161, v165
	v_pk_add_f32 v[178:179], v[158:159], v[160:161]
	v_pk_add_f32 v[174:175], v[158:159], v[160:161] neg_lo:[0,1] neg_hi:[0,1]
	v_pk_add_f32 v[158:159], v[178:179], v[136:137] op_sel:[1,0] op_sel_hi:[0,1] neg_lo:[0,1] neg_hi:[0,1]
	v_pk_add_f32 v[160:161], v[164:165], v[158:159] op_sel_hi:[1,0] neg_lo:[0,1] neg_hi:[0,1]
	v_pk_mov_b32 v[158:159], v[136:137], v[158:159] op_sel:[1,0]
	v_mov_b32_e32 v162, v163
	v_mov_b32_e32 v163, v136
	v_mul_f32_e32 v136, 0xbfb8aa3b, v138
	v_fma_f32 v137, v138, s24, -v136
	v_rndne_f32_e32 v145, v136
	v_fmac_f32_e32 v137, 0xb2a5705f, v138
	v_sub_f32_e32 v136, v136, v145
	v_add_f32_e32 v136, v136, v137
	v_exp_f32_e32 v136, v136
	v_cvt_i32_f32_e32 v137, v145
	v_mov_b32_e32 v178, v165
	v_pk_add_f32 v[158:159], v[178:179], v[158:159] neg_lo:[0,1] neg_hi:[0,1]
	v_mov_b32_e32 v160, v174
	v_ldexp_f32 v136, v136, v137
	v_cndmask_b32_e32 v136, 0, v136, vcc
	v_cmp_ngt_f32_e32 vcc, s26, v138
	v_pk_add_f32 v[176:177], v[162:163], v[158:159] neg_lo:[0,1] neg_hi:[0,1]
	v_mul_f32_e32 v72, 0xbfb8aa3b, v72
	v_cndmask_b32_e32 v145, v209, v136, vcc
	v_add_f32_e32 v138, 1.0, v145
	v_add_f32_e32 v136, -1.0, v138
	v_sub_f32_e32 v137, v136, v138
	v_add_f32_e32 v137, 1.0, v137
	v_sub_f32_e32 v136, v145, v136
	v_add_f32_e32 v149, v136, v137
	v_frexp_mant_f32_e32 v136, v138
	v_cmp_gt_f32_e32 vcc, s37, v136
	v_cvt_f64_f32_e32 v[136:137], v138
	v_frexp_exp_i32_f64_e32 v136, v[136:137]
	v_subbrev_co_u32_e32 v152, vcc, 0, v136, vcc
	v_sub_u32_e32 v136, 0, v152
	v_ldexp_f32 v138, v138, v136
	v_ldexp_f32 v136, v149, v136
	v_add_f32_e32 v149, -1.0, v138
	v_add_f32_e32 v137, 1.0, v149
	v_sub_f32_e32 v137, v138, v137
	v_add_f32_e32 v155, v136, v137
	v_add_f32_e32 v137, v149, v155
	v_sub_f32_e32 v149, v149, v137
	v_add_f32_e32 v149, v155, v149
	v_add_f32_e32 v155, 1.0, v138
	v_add_f32_e32 v158, -1.0, v155
	v_sub_f32_e32 v138, v138, v158
	v_add_f32_e32 v136, v136, v138
	v_add_f32_e32 v138, v155, v136
	v_rcp_f32_e32 v164, v138
	v_sub_f32_e32 v155, v155, v138
	v_pk_add_f32 v[180:181], v[160:161], v[176:177]
	v_add_f32_e32 v155, v136, v155
	v_mul_f32_e32 v165, v137, v164
	v_mul_f32_e32 v158, v138, v165
	v_fma_f32 v160, v165, v138, -v158
	v_fmac_f32_e32 v160, v165, v155
	v_add_f32_e32 v136, v158, v160
	v_sub_f32_e32 v159, v137, v136
	v_pk_add_f32 v[162:163], v[136:137], v[158:159] neg_lo:[0,1] neg_hi:[0,1]
	v_mov_b32_e32 v161, v136
	v_pk_add_f32 v[136:137], v[162:163], v[160:161] neg_lo:[0,1] neg_hi:[0,1]
	v_cmp_nlt_f32_e32 vcc, s25, v139
	v_add_f32_e32 v137, v149, v137
	v_add_f32_e32 v136, v136, v137
	v_add_f32_e32 v137, v159, v136
	v_mul_f32_e32 v149, v164, v137
	v_mul_f32_e32 v158, v138, v149
	v_fma_f32 v160, v149, v138, -v158
	v_fmac_f32_e32 v160, v149, v155
	v_sub_f32_e32 v138, v159, v137
	v_add_f32_e32 v138, v136, v138
	v_add_f32_e32 v136, v158, v160
	v_sub_f32_e32 v159, v137, v136
	v_pk_add_f32 v[162:163], v[136:137], v[158:159] neg_lo:[0,1] neg_hi:[0,1]
	v_mov_b32_e32 v161, v136
	v_pk_add_f32 v[136:137], v[162:163], v[160:161] neg_lo:[0,1] neg_hi:[0,1]
	v_exp_f32_e32 v72, v72
	v_add_f32_e32 v137, v138, v137
	v_add_f32_e32 v136, v136, v137
	v_add_f32_e32 v137, v165, v149
	v_add_f32_e32 v136, v159, v136
	v_sub_f32_e32 v138, v137, v165
	v_mul_f32_e32 v136, v164, v136
	v_sub_f32_e32 v138, v149, v138
	v_add_f32_e32 v138, v138, v136
	v_add_f32_e32 v155, v137, v138
	v_mul_f32_e32 v158, v155, v155
	v_fmamk_f32 v136, v158, 0x3e9b6dac, v195
	v_fmaak_f32 v149, v158, v136, 0x3f2aaada
	v_cvt_f32_i32_e32 v136, v152
	v_sub_f32_e32 v137, v155, v137
	v_sub_f32_e32 v137, v138, v137
	v_ldexp_f32 v138, v137, 1
	v_mul_f32_e32 v137, v155, v158
	v_pk_mul_f32 v[158:159], v[136:137], v[148:149]
	v_ldexp_f32 v161, v155, 1
	v_fma_f32 v160, v136, s38, -v158
	v_fmac_f32_e32 v160, 0xb102e308, v136
	v_pk_add_f32 v[136:137], v[158:159], v[160:161]
	v_mov_b32_e32 v162, v158
	v_sub_f32_e32 v149, v137, v161
	v_sub_f32_e32 v149, v159, v149
	v_add_f32_e32 v163, v138, v149
	v_pk_add_f32 v[164:165], v[136:137], v[158:159] neg_lo:[0,1] neg_hi:[0,1]
	v_pk_add_f32 v[166:167], v[136:137], v[162:163]
	v_mov_b32_e32 v161, v136
	v_mov_b32_e32 v165, v167
	v_pk_add_f32 v[158:159], v[160:161], v[164:165] neg_lo:[0,1] neg_hi:[0,1]
	v_pk_add_f32 v[160:161], v[160:161], v[164:165]
	v_mov_b32_e32 v162, v163
	v_pk_add_f32 v[164:165], v[160:161], v[136:137] op_sel:[1,0] op_sel_hi:[0,1] neg_lo:[0,1] neg_hi:[0,1]
	v_pk_add_f32 v[168:169], v[166:167], v[164:165] op_sel_hi:[1,0] neg_lo:[0,1] neg_hi:[0,1]
	v_pk_mov_b32 v[164:165], v[136:137], v[164:165] op_sel:[1,0]
	v_mov_b32_e32 v163, v136
	v_mul_f32_e32 v136, 0xbfb8aa3b, v139
	v_fma_f32 v137, v139, s24, -v136
	v_rndne_f32_e32 v138, v136
	v_fmac_f32_e32 v137, 0xb2a5705f, v139
	v_sub_f32_e32 v136, v136, v138
	v_add_f32_e32 v136, v136, v137
	v_exp_f32_e32 v136, v136
	v_cvt_i32_f32_e32 v137, v138
	v_mov_b32_e32 v160, v167
	v_pk_add_f32 v[164:165], v[160:161], v[164:165] neg_lo:[0,1] neg_hi:[0,1]
	v_mov_b32_e32 v168, v158
	v_ldexp_f32 v136, v136, v137
	v_cndmask_b32_e32 v136, 0, v136, vcc
	v_cmp_ngt_f32_e32 vcc, s26, v139
	v_pk_add_f32 v[162:163], v[162:163], v[164:165] neg_lo:[0,1] neg_hi:[0,1]
	v_add_f32_e32 v112, 1.0, v112
	v_cndmask_b32_e32 v178, v209, v136, vcc
	v_add_f32_e32 v138, 1.0, v178
	v_add_f32_e32 v136, -1.0, v138
	v_sub_f32_e32 v137, v136, v138
	v_add_f32_e32 v137, 1.0, v137
	v_sub_f32_e32 v136, v178, v136
	v_add_f32_e32 v139, v136, v137
	v_frexp_mant_f32_e32 v136, v138
	v_cmp_gt_f32_e32 vcc, s37, v136
	v_cvt_f64_f32_e32 v[136:137], v138
	v_frexp_exp_i32_f64_e32 v136, v[136:137]
	v_subbrev_co_u32_e32 v152, vcc, 0, v136, vcc
	v_sub_u32_e32 v136, 0, v152
	v_ldexp_f32 v138, v138, v136
	v_ldexp_f32 v136, v139, v136
	v_add_f32_e32 v139, -1.0, v138
	v_add_f32_e32 v137, 1.0, v139
	v_sub_f32_e32 v137, v138, v137
	v_add_f32_e32 v149, v136, v137
	v_add_f32_e32 v137, v139, v149
	v_sub_f32_e32 v139, v139, v137
	v_add_f32_e32 v149, v149, v139
	v_add_f32_e32 v139, 1.0, v138
	v_add_f32_e32 v155, -1.0, v139
	v_sub_f32_e32 v138, v138, v155
	v_add_f32_e32 v136, v136, v138
	v_add_f32_e32 v155, v139, v136
	v_pk_add_f32 v[164:165], v[168:169], v[162:163]
	v_rcp_f32_e32 v163, v155
	v_sub_f32_e32 v138, v139, v155
	v_add_f32_e32 v160, v136, v138
	v_rcp_f32_e32 v247, v112
	v_mul_f32_e32 v170, v137, v163
	v_mul_f32_e32 v138, v155, v170
	v_fma_f32 v166, v170, v155, -v138
	v_fmac_f32_e32 v166, v170, v160
	v_add_f32_e32 v136, v138, v166
	v_sub_f32_e32 v139, v137, v136
	v_pk_add_f32 v[168:169], v[136:137], v[138:139] neg_lo:[0,1] neg_hi:[0,1]
	v_mov_b32_e32 v167, v136
	v_pk_add_f32 v[136:137], v[168:169], v[166:167] neg_lo:[0,1] neg_hi:[0,1]
	s_waitcnt vmcnt(0)
	v_add_f32_e32 v112, v117, v89
	v_add_f32_e32 v137, v149, v137
	v_add_f32_e32 v136, v136, v137
	v_add_f32_e32 v137, v139, v136
	v_mul_f32_e32 v149, v163, v137
	v_mul_f32_e32 v138, v155, v149
	v_fma_f32 v166, v149, v155, -v138
	v_fmac_f32_e32 v166, v149, v160
	v_sub_f32_e32 v139, v139, v137
	v_add_f32_e32 v155, v136, v139
	v_add_f32_e32 v136, v138, v166
	v_sub_f32_e32 v139, v137, v136
	v_pk_add_f32 v[168:169], v[136:137], v[138:139] neg_lo:[0,1] neg_hi:[0,1]
	v_mov_b32_e32 v167, v136
	v_pk_add_f32 v[136:137], v[168:169], v[166:167] neg_lo:[0,1] neg_hi:[0,1]
	v_mul_f32_e32 v112, 0xbfb8aa3b, v112
	v_add_f32_e32 v137, v155, v137
	v_add_f32_e32 v136, v136, v137
	v_add_f32_e32 v137, v170, v149
	v_add_f32_e32 v136, v139, v136
	v_sub_f32_e32 v138, v137, v170
	v_mul_f32_e32 v136, v163, v136
	v_sub_f32_e32 v138, v149, v138
	v_add_f32_e32 v138, v138, v136
	v_add_f32_e32 v139, v137, v138
	v_mul_f32_e32 v155, v139, v139
	v_fmamk_f32 v136, v155, 0x3e9b6dac, v195
	v_fmaak_f32 v149, v155, v136, 0x3f2aaada
	v_cvt_f32_i32_e32 v136, v152
	v_sub_f32_e32 v137, v139, v137
	v_sub_f32_e32 v137, v138, v137
	v_ldexp_f32 v152, v137, 1
	v_mul_f32_e32 v137, v139, v155
	v_ldexp_f32 v167, v139, 1
	v_pk_mul_f32 v[138:139], v[136:137], v[148:149]
	v_add_f32_e32 v72, 1.0, v72
	v_fma_f32 v166, v136, s38, -v138
	v_fmac_f32_e32 v166, 0xb102e308, v136
	v_pk_add_f32 v[136:137], v[138:139], v[166:167]
	v_mov_b32_e32 v168, v138
	v_sub_f32_e32 v149, v137, v167
	v_sub_f32_e32 v149, v139, v149
	v_add_f32_e32 v169, v152, v149
	v_pk_add_f32 v[170:171], v[136:137], v[138:139] neg_lo:[0,1] neg_hi:[0,1]
	v_pk_add_f32 v[200:201], v[136:137], v[168:169]
	v_mov_b32_e32 v167, v136
	v_mov_b32_e32 v171, v201
	v_pk_add_f32 v[138:139], v[166:167], v[170:171] neg_lo:[0,1] neg_hi:[0,1]
	v_pk_add_f32 v[170:171], v[166:167], v[170:171]
	v_mov_b32_e32 v168, v169
	v_pk_add_f32 v[166:167], v[170:171], v[136:137] op_sel:[1,0] op_sel_hi:[0,1] neg_lo:[0,1] neg_hi:[0,1]
	v_pk_add_f32 v[206:207], v[200:201], v[166:167] op_sel_hi:[1,0] neg_lo:[0,1] neg_hi:[0,1]
	v_pk_mov_b32 v[166:167], v[136:137], v[166:167] op_sel:[1,0]
	v_mov_b32_e32 v169, v136
	v_lshl_add_u64 v[136:137], v[182:183], 1, v[140:141]
	v_add_co_u32_e32 v200, vcc, s33, v136
	v_mov_b32_e32 v170, v201
	s_nop 0
	v_addc_co_u32_e32 v201, vcc, 0, v137, vcc
	global_load_dwordx2 v[182:183], v[136:137], off
	v_pk_add_f32 v[166:167], v[170:171], v[166:167] neg_lo:[0,1] neg_hi:[0,1]
	global_load_dwordx2 v[200:201], v[200:201], off
	v_pk_add_f32 v[166:167], v[168:169], v[166:167] neg_lo:[0,1] neg_hi:[0,1]
	v_mov_b32_e32 v206, v138
	v_pk_add_f32 v[168:169], v[206:207], v[166:167]
	v_rcp_f32_e32 v167, v128
	v_add_f32_e32 v128, v133, v89
	v_mul_f32_e32 v128, 0xbfb8aa3b, v128
	v_exp_f32_e32 v128, v128
	v_add_f32_e32 v121, v121, v93
	v_exp_f32_e32 v112, v112
	v_rcp_f32_e32 v203, v72
	v_add_f32_e32 v128, 1.0, v128
	v_rcp_f32_e32 v128, v128
	v_add_f32_e32 v72, v77, v89
	v_mul_f32_e32 v121, 0xbfb8aa3b, v121
	v_mul_f32_e32 v72, 0xbfb8aa3b, v72
	v_mul_f32_e32 v241, 0xc1000000, v128
	v_add_f32_e32 v128, v134, v90
	v_exp_f32_e32 v121, v121
	v_exp_f32_e32 v72, v72
	v_mul_f32_e32 v128, 0xbfb8aa3b, v128
	v_exp_f32_e32 v128, v128
	v_add_f32_e32 v120, v120, v92
	v_add_f32_e32 v112, 1.0, v112
	v_add_f32_e32 v96, v96, v92
	v_mul_f32_e32 v120, 0xbfb8aa3b, v120
	v_rcp_f32_e32 v112, v112
	v_mul_f32_e32 v96, 0xbfb8aa3b, v96
	v_exp_f32_e32 v120, v120
	v_add_f32_e32 v121, 1.0, v121
	v_add_f32_e32 v104, v104, v92
	v_exp_f32_e32 v96, v96
	v_add_f32_e32 v73, v73, v93
	v_add_f32_e32 v72, 1.0, v72
	v_rcp_f32_e32 v244, v121
	v_add_f32_e32 v121, v122, v94
	v_mul_f32_e32 v104, 0xbfb8aa3b, v104
	v_rcp_f32_e32 v122, v72
	v_mul_f32_e32 v72, 0xbfb8aa3b, v73
	v_add_f32_e32 v128, 1.0, v128
	v_exp_f32_e32 v104, v104
	v_exp_f32_e32 v72, v72
	v_rcp_f32_e32 v128, v128
	v_mul_f32_e32 v250, 0xc1000000, v112
	v_add_f32_e32 v112, v118, v90
	v_add_f32_e32 v120, 1.0, v120
	v_mul_f32_e32 v112, 0xbfb8aa3b, v112
	v_add_f32_e32 v96, 1.0, v96
	v_add_f32_e32 v129, v129, v93
	v_rcp_f32_e32 v243, v120
	v_add_f32_e32 v120, v125, v89
	v_exp_f32_e32 v112, v112
	v_rcp_f32_e32 v199, v96
	v_add_f32_e32 v96, v101, v89
	v_mul_f32_e32 v129, 0xbfb8aa3b, v129
	v_mul_f32_e32 v120, 0xbfb8aa3b, v120
	v_add_f32_e32 v104, 1.0, v104
	v_mul_f32_e32 v96, 0xbfb8aa3b, v96
	v_add_f32_e32 v72, 1.0, v72
	v_exp_f32_e32 v129, v129
	v_mul_f32_e32 v215, 0xc1000000, v128
	v_add_f32_e32 v128, v135, v91
	v_exp_f32_e32 v120, v120
	v_rcp_f32_e32 v251, v104
	v_add_f32_e32 v104, v109, v89
	v_exp_f32_e32 v96, v96
	v_rcp_f32_e32 v208, v72
	v_add_f32_e32 v72, v78, v90
	v_mul_f32_e32 v128, 0xbfb8aa3b, v128
	v_mul_f32_e32 v104, 0xbfb8aa3b, v104
	v_mul_f32_e32 v72, 0xbfb8aa3b, v72
	v_add_f32_e32 v64, v64, v88
	v_exp_f32_e32 v128, v128
	v_add_f32_e32 v112, 1.0, v112
	v_exp_f32_e32 v104, v104
	v_exp_f32_e32 v72, v72
	v_mul_f32_e32 v64, 0xbfb8aa3b, v64
	v_rcp_f32_e32 v112, v112
	v_exp_f32_e32 v64, v64
	v_add_f32_e32 v129, 1.0, v129
	v_add_f32_e32 v120, 1.0, v120
	v_add_f32_e32 v96, 1.0, v96
	v_rcp_f32_e32 v238, v129
	v_add_f32_e32 v129, v130, v94
	v_rcp_f32_e32 v120, v120
	v_rcp_f32_e32 v96, v96
	v_add_f32_e32 v132, v132, v88
	v_mul_f32_e32 v129, 0xbfb8aa3b, v129
	v_add_f32_e32 v128, 1.0, v128
	v_add_f32_e32 v104, 1.0, v104
	v_add_f32_e32 v73, v74, v94
	v_add_f32_e32 v72, 1.0, v72
	v_mul_f32_e32 v132, 0xbfb8aa3b, v132
	v_exp_f32_e32 v129, v129
	v_rcp_f32_e32 v128, v128
	v_mul_f32_e32 v223, 0xc1000000, v112
	v_add_f32_e32 v112, v119, v91
	v_rcp_f32_e32 v104, v104
	v_add_f32_e32 v98, v98, v94
	v_rcp_f32_e32 v119, v72
	v_mul_f32_e32 v72, 0xbfb8aa3b, v73
	v_add_f32_e32 v68, v68, v92
	v_add_f32_e32 v64, 1.0, v64
	v_exp_f32_e32 v132, v132
	v_mul_f32_e32 v98, 0xbfb8aa3b, v98
	v_exp_f32_e32 v72, v72
	v_rcp_f32_e32 v77, v64
	v_mul_f32_e32 v64, 0xbfb8aa3b, v68
	v_mul_f32_e32 v246, 0xc1000000, v120
	v_add_f32_e32 v120, v126, v90
	v_mul_f32_e32 v101, 0xc1000000, v96
	v_add_f32_e32 v96, v102, v90
	v_exp_f32_e32 v98, v98
	v_exp_f32_e32 v64, v64
	v_mul_f32_e32 v120, 0xbfb8aa3b, v120
	v_mul_f32_e32 v96, 0xbfb8aa3b, v96
	s_waitcnt vmcnt(1)
	v_lshlrev_b32_e32 v163, 16, v182
	v_and_b32_e32 v160, 0xffff0000, v182
	v_add_f32_e32 v129, 1.0, v129
	v_mul_f32_e32 v216, 0xc1000000, v128
	v_ashrrev_i32_e32 v128, 5, v172
	v_lshlrev_b32_e32 v130, 4, v172
	s_waitcnt vmcnt(0)
	v_lshlrev_b32_e32 v182, 16, v201
	v_and_b32_e32 v172, 0xffff0000, v201
	v_exp_f32_e32 v120, v120
	v_mul_f32_e32 v201, 0xc1000000, v104
	v_add_f32_e32 v104, v110, v90
	v_exp_f32_e32 v96, v96
	v_add_f32_e32 v84, v84, v88
	v_add_f32_e32 v132, 1.0, v132
	v_rcp_f32_e32 v214, v129
	v_add_f32_e32 v129, v131, v95
	v_mul_f32_e32 v104, 0xbfb8aa3b, v104
	v_mul_f32_e32 v84, 0xbfb8aa3b, v84
	v_add_f32_e32 v72, 1.0, v72
	v_rcp_f32_e32 v132, v132
	v_mul_f32_e32 v129, 0xbfb8aa3b, v129
	v_exp_f32_e32 v104, v104
	v_add_f32_e32 v98, 1.0, v98
	v_exp_f32_e32 v84, v84
	v_add_f32_e32 v81, v81, v93
	v_rcp_f32_e32 v236, v72
	v_add_f32_e32 v72, v79, v91
	v_add_f32_e32 v64, 1.0, v64
	v_exp_f32_e32 v129, v129
	v_rcp_f32_e32 v230, v98
	v_add_f32_e32 v98, v99, v95
	v_mul_f32_e32 v81, 0xbfb8aa3b, v81
	v_add_f32_e32 v76, v76, v88
	v_mul_f32_e32 v72, 0xbfb8aa3b, v72
	v_rcp_f32_e32 v68, v64
	v_add_f32_e32 v64, v65, v89
	v_add_f32_e32 v120, 1.0, v120
	v_mul_f32_e32 v121, 0xbfb8aa3b, v121
	v_add_f32_e32 v96, 1.0, v96
	v_mul_f32_e32 v98, 0xbfb8aa3b, v98
	v_add_f32_e32 v80, v80, v92
	v_exp_f32_e32 v81, v81
	v_mul_f32_e32 v76, 0xbfb8aa3b, v76
	v_exp_f32_e32 v72, v72
	v_mul_f32_e32 v64, 0xbfb8aa3b, v64
	v_rcp_f32_e32 v120, v120
	v_exp_f32_e32 v121, v121
	v_add_f32_e32 v116, v116, v88
	v_rcp_f32_e32 v96, v96
	v_exp_f32_e32 v98, v98
	v_mul_f32_e32 v80, 0xbfb8aa3b, v80
	v_add_f32_e32 v82, v82, v94
	v_exp_f32_e32 v76, v76
	v_exp_f32_e32 v64, v64
	v_ashrrev_i32_e32 v152, 4, v142
	v_mul_f32_e32 v240, 0xc1000000, v132
	v_and_b32_e32 v132, 0xffffff80, v128
	v_mul_f32_e32 v116, 0xbfb8aa3b, v116
	v_add_f32_e32 v113, v113, v93
	v_add_f32_e32 v104, 1.0, v104
	v_add_f32_e32 v84, 1.0, v84
	v_exp_f32_e32 v80, v80
	v_mul_f32_e32 v82, 0xbfb8aa3b, v82
	v_add_f32_e32 v129, 1.0, v129
	v_add_u32_e32 v128, v132, v152
	v_exp_f32_e32 v116, v116
	v_mul_f32_e32 v113, 0xbfb8aa3b, v113
	v_rcp_f32_e32 v104, v104
	v_rcp_f32_e32 v84, v84
	v_exp_f32_e32 v82, v82
	v_lshlrev_b32_e32 v170, 16, v183
	v_and_b32_e32 v149, 0xffff0000, v183
	v_rcp_f32_e32 v183, v129
	v_ashrrev_i32_e32 v129, 31, v128
	v_and_b32_e32 v133, 0xf8f0, v130
	v_exp_f32_e32 v113, v113
	v_add_f32_e32 v81, 1.0, v81
	v_add_f32_e32 v73, v75, v95
	v_add_f32_e32 v72, 1.0, v72
	v_lshlrev_b64 v[128:129], 16, v[128:129]
	v_add_f32_e32 v121, 1.0, v121
	v_mul_f32_e32 v219, 0xc1000000, v120
	v_add_f32_e32 v120, v127, v91
	v_mul_f32_e32 v231, 0xc1000000, v96
	v_add_f32_e32 v96, v103, v91
	v_add_f32_e32 v98, 1.0, v98
	v_or_b32_e32 v127, 0x400, v133
	v_rcp_f32_e32 v103, v81
	v_add_f32_e32 v81, v86, v90
	v_add_f32_e32 v76, 1.0, v76
	v_rcp_f32_e32 v118, v72
	v_mul_f32_e32 v72, 0xbfb8aa3b, v73
	v_add_f32_e32 v65, v69, v93
	v_add_f32_e32 v64, 1.0, v64
	v_rcp_f32_e32 v218, v121
	v_add_f32_e32 v121, v123, v95
	v_rcp_f32_e32 v229, v98
	v_or3_b32 v98, v128, v127, v146
	v_mov_b32_e32 v99, v129
	v_add_f32_e32 v80, 1.0, v80
	v_mul_f32_e32 v81, 0xbfb8aa3b, v81
	v_rcp_f32_e32 v123, v76
	v_exp_f32_e32 v72, v72
	v_rcp_f32_e32 v76, v64
	v_mul_f32_e32 v64, 0xbfb8aa3b, v65
	v_add_f32_e32 v116, 1.0, v116
	v_mul_f32_e32 v227, 0xc1000000, v104
	v_add_f32_e32 v104, v111, v91
	v_lshl_add_u64 v[110:111], v[98:99], 3, s[14:15]
	v_rcp_f32_e32 v99, v80
	v_mul_f32_e32 v80, 0xc1000000, v84
	v_add_f32_e32 v84, v85, v89
	v_exp_f32_e32 v81, v81
	v_add_f32_e32 v82, 1.0, v82
	v_exp_f32_e32 v64, v64
	v_rcp_f32_e32 v116, v116
	v_add_f32_e32 v113, 1.0, v113
	v_mul_f32_e32 v84, 0xbfb8aa3b, v84
	v_rcp_f32_e32 v234, v82
	v_add_f32_e32 v82, v83, v95
	v_rcp_f32_e32 v248, v113
	v_add_f32_e32 v113, v114, v94
	v_exp_f32_e32 v84, v84
	v_mul_f32_e32 v82, 0xbfb8aa3b, v82
	v_mul_f32_e32 v113, 0xbfb8aa3b, v113
	v_exp_f32_e32 v82, v82
	v_add_f32_e32 v72, 1.0, v72
	v_or_b32_e32 v135, 0x600, v133
	v_exp_f32_e32 v113, v113
	v_add_f32_e32 v81, 1.0, v81
	v_rcp_f32_e32 v79, v72
	v_or3_b32 v72, v128, v135, v146
	v_mov_b32_e32 v73, v129
	v_add_f32_e32 v64, 1.0, v64
	v_mul_f32_e32 v249, 0xc1000000, v116
	v_rcp_f32_e32 v81, v81
	v_lshl_add_u64 v[116:117], v[72:73], 3, s[14:15]
	v_rcp_f32_e32 v189, v64
	v_mov_b32_e32 v64, v180
	v_mov_b32_e32 v65, v156
	v_mov_b32_e32 v72, v181
	v_mov_b32_e32 v73, v157
	v_add_f32_e32 v84, 1.0, v84
	v_pk_add_f32 v[72:73], v[64:65], v[72:73]
	v_mov_b32_e32 v152, v179
	v_rcp_f32_e32 v84, v84
	v_add_f32_e32 v82, 1.0, v82
	v_or_b32_e32 v134, 0x500, v133
	v_pk_add_f32 v[74:75], v[152:153], v[72:73]
	v_mov_b32_e32 v151, v153
	v_mov_b32_e32 v175, v179
	v_add_f32_e32 v113, 1.0, v113
	v_rcp_f32_e32 v233, v82
	v_or3_b32 v82, v128, v134, v146
	v_mov_b32_e32 v83, v129
	v_mov_b32_e32 v157, v75
	v_mov_b32_e32 v181, v74
	v_rcp_f32_e32 v222, v113
	v_add_f32_e32 v113, v115, v95
	v_mul_f32_e32 v235, 0xc1000000, v81
	v_add_f32_e32 v81, v87, v91
	v_lshl_add_u64 v[114:115], v[82:83], 3, s[14:15]
	v_pk_add_f32 v[82:83], v[156:157], v[150:151] neg_lo:[0,1] neg_hi:[0,1]
	v_pk_add_f32 v[86:87], v[180:181], v[174:175] neg_lo:[0,1] neg_hi:[0,1]
	v_add_f32_e32 v124, v124, v88
	v_add_f32_e32 v108, v108, v88
	v_add_f32_e32 v100, v100, v88
	v_mov_b32_e32 v155, v73
	v_mov_b32_e32 v88, v86
	v_mov_b32_e32 v89, v82
	v_mov_b32_e32 v177, v72
	v_mul_f32_e32 v207, 0xc1000000, v84
	v_pk_add_f32 v[84:85], v[154:155], v[82:83] neg_lo:[0,1] neg_hi:[0,1]
	v_pk_add_f32 v[64:65], v[64:65], v[88:89] neg_lo:[0,1] neg_hi:[0,1]
	v_mov_b32_e32 v175, v150
	v_pk_add_f32 v[72:73], v[176:177], v[86:87] neg_lo:[0,1] neg_hi:[0,1]
	v_pk_add_f32 v[64:65], v[174:175], v[64:65] neg_lo:[0,1] neg_hi:[0,1]
	v_mov_b32_e32 v82, v72
	v_mov_b32_e32 v83, v84
	v_pk_add_f32 v[64:65], v[82:83], v[64:65]
	v_mov_b32_e32 v84, v73
	v_pk_add_f32 v[64:65], v[64:65], v[84:85]
	v_cmp_neq_f32_e32 vcc, s27, v173
	v_pk_add_f32 v[64:65], v[74:75], v[64:65]
	v_cmp_lt_f32_e64 s[0:1], |v143|, s39
	v_cndmask_b32_e32 v64, v209, v64, vcc
	v_cmp_neq_f32_e32 vcc, s27, v143
	v_add_f32_e32 v105, v105, v93
	v_mul_f32_e32 v105, 0xbfb8aa3b, v105
	v_cndmask_b32_e32 v65, v209, v65, vcc
	v_cndmask_b32_e64 v65, v65, v143, s[0:1]
	v_mul_f32_e32 v69, v240, v65
	v_mul_f32_e32 v72, 0x3fb8aa3b, v69
	v_exp_f32_e32 v72, v72
	v_add_f32_e32 v69, v69, v69
	v_fmamk_f32 v74, v69, 0x3d2aaaab, v196
	v_fma_f32 v74, v69, v74, 0.5
	v_cmp_lt_f32_e64 vcc, |v173|, s39
	v_fma_f32 v74, v69, v74, 1.0
	v_fma_f32 v73, -v72, v72, 1.0
	v_cndmask_b32_e32 v64, v64, v173, vcc
	v_mul_f32_e64 v74, v74, -v69
	v_cmp_lt_f32_e32 vcc, s40, v69
	v_exp_f32_e32 v105, v105
	v_mul_f32_e32 v124, 0xbfb8aa3b, v124
	v_cndmask_b32_e32 v69, v73, v74, vcc
	v_max_f32_e32 v69, 0, v69
	v_sqrt_f32_e32 v69, v69
	v_add_f32_e32 v105, 1.0, v105
	v_rcp_f32_e32 v252, v105
	v_add_f32_e32 v105, v106, v94
	v_mul_f32_e32 v69, v167, v69
	v_mul_f32_e32 v73, v69, v163
	v_mul_f32_e32 v69, v241, v64
	v_mul_f32_e32 v74, 0x3fb8aa3b, v69
	v_mul_f32_e32 v105, 0xbfb8aa3b, v105
	v_exp_f32_e32 v74, v74
	v_add_f32_e32 v69, v69, v69
	v_exp_f32_e32 v105, v105
	v_fmamk_f32 v78, v69, 0x3d2aaaab, v196
	v_exp_f32_e32 v124, v124
	v_fma_f32 v78, v69, v78, 0.5
	v_mul_f32_e32 v104, 0xbfb8aa3b, v104
	v_fma_f32 v78, v69, v78, 1.0
	v_mul_f32_e32 v108, 0xbfb8aa3b, v108
	v_exp_f32_e32 v104, v104
	v_fma_f32 v75, -v74, v74, 1.0
	v_mul_f32_e64 v78, v78, -v69
	v_cmp_lt_f32_e32 vcc, s40, v69
	v_exp_f32_e32 v108, v108
	v_add_f32_e32 v105, 1.0, v105
	v_cndmask_b32_e32 v69, v75, v78, vcc
	v_add_f32_e32 v124, 1.0, v124
	v_rcp_f32_e32 v226, v105
	v_add_f32_e32 v105, v107, v95
	v_max_f32_e32 v69, 0, v69
	v_rcp_f32_e32 v124, v124
	v_mul_f32_e32 v105, 0xbfb8aa3b, v105
	v_sqrt_f32_e32 v69, v69
	v_add_f32_e32 v104, 1.0, v104
	v_exp_f32_e32 v105, v105
	v_add_f32_e32 v108, 1.0, v108
	v_rcp_f32_e32 v104, v104
	v_rcp_f32_e32 v108, v108
	v_or3_b32 v130, v128, v133, v146
	v_mov_b32_e32 v131, v129
	v_mul_f32_e32 v245, 0xc1000000, v124
	v_mul_f32_e32 v69, v238, v69
	v_lshl_add_u64 v[130:131], v[130:131], 3, s[14:15]
	v_add_f32_e32 v105, 1.0, v105
	v_or_b32_e32 v126, 0x300, v133
	v_mul_f32_e32 v75, v69, v160
	v_mul_f32_e32 v69, v245, v65
	v_rcp_f32_e32 v225, v105
	v_mul_f32_e32 v228, 0xc1000000, v104
	v_or3_b32 v104, v128, v126, v146
	v_mov_b32_e32 v105, v129
	global_store_dwordx4 v[130:131], v[72:75], off
	v_lshlrev_b32_e32 v242, 16, v200
	v_and_b32_e32 v239, 0xffff0000, v200
	v_mul_f32_e32 v72, 0x3fb8aa3b, v69
	v_mul_f32_e32 v200, 0xc1000000, v108
	v_lshl_add_u64 v[108:109], v[104:105], 3, s[14:15]
	v_exp_f32_e32 v104, v72
	v_add_f32_e32 v69, v69, v69
	v_fmamk_f32 v73, v69, 0x3d2aaaab, v196
	v_fma_f32 v73, v69, v73, 0.5
	v_fma_f32 v73, v69, v73, 1.0
	v_fma_f32 v72, -v104, v104, 1.0
	v_mul_f32_e64 v73, v73, -v69
	v_cmp_lt_f32_e32 vcc, s40, v69
	v_mul_f32_e32 v100, 0xbfb8aa3b, v100
	v_exp_f32_e32 v100, v100
	v_cndmask_b32_e32 v69, v72, v73, vcc
	v_max_f32_e32 v69, 0, v69
	v_sqrt_f32_e32 v69, v69
	v_add_f32_e32 v100, 1.0, v100
	v_rcp_f32_e32 v100, v100
	v_mul_f32_e32 v96, 0xbfb8aa3b, v96
	v_mul_f32_e32 v69, v243, v69
	v_mul_f32_e32 v105, v69, v242
	v_mul_f32_e32 v69, v246, v64
	v_mul_f32_e32 v72, 0x3fb8aa3b, v69
	v_exp_f32_e32 v106, v72
	v_add_f32_e32 v69, v69, v69
	v_fmamk_f32 v73, v69, 0x3d2aaaab, v196
	v_fma_f32 v73, v69, v73, 0.5
	v_fma_f32 v73, v69, v73, 1.0
	v_fma_f32 v72, -v106, v106, 1.0
	v_mul_f32_e64 v73, v73, -v69
	v_cmp_lt_f32_e32 vcc, s40, v69
	v_mul_f32_e32 v206, 0xc1000000, v100
	v_exp_f32_e32 v96, v96
	v_cndmask_b32_e32 v69, v72, v73, vcc
	v_max_f32_e32 v69, 0, v69
	v_sqrt_f32_e32 v69, v69
	v_add_f32_e32 v96, 1.0, v96
	v_rcp_f32_e32 v96, v96
	v_add_f32_e32 v97, v97, v93
	v_mul_f32_e32 v69, v244, v69
	v_mul_f32_e32 v107, v69, v239
	v_mul_f32_e32 v69, v249, v65
	v_mul_f32_e32 v72, 0x3fb8aa3b, v69
	v_exp_f32_e32 v100, v72
	v_add_f32_e32 v69, v69, v69
	v_fmamk_f32 v73, v69, 0x3d2aaaab, v196
	v_fma_f32 v73, v69, v73, 0.5
	v_fma_f32 v73, v69, v73, 1.0
	v_fma_f32 v72, -v100, v100, 1.0
	v_mul_f32_e64 v73, v73, -v69
	v_cmp_lt_f32_e32 vcc, s40, v69
	v_mul_f32_e32 v232, 0xc1000000, v96
	v_mul_f32_e32 v81, 0xbfb8aa3b, v81
	v_cndmask_b32_e32 v69, v72, v73, vcc
	v_max_f32_e32 v69, 0, v69
	v_sqrt_f32_e32 v69, v69
	v_exp_f32_e32 v81, v81
	v_mul_f32_e32 v97, 0xbfb8aa3b, v97
	v_exp_f32_e32 v97, v97
	v_mul_f32_e32 v92, v247, v69
	v_mul_f32_e32 v69, v250, v64
	v_mul_f32_e32 v72, 0x3fb8aa3b, v69
	v_exp_f32_e32 v102, v72
	v_add_f32_e32 v69, v69, v69
	v_fmamk_f32 v73, v69, 0x3d2aaaab, v196
	v_fma_f32 v73, v69, v73, 0.5
	v_fma_f32 v73, v69, v73, 1.0
	v_fma_f32 v72, -v102, v102, 1.0
	v_mul_f32_e64 v73, v73, -v69
	v_cmp_lt_f32_e32 vcc, s40, v69
	v_add_f32_e32 v81, 1.0, v81
	v_rcp_f32_e32 v81, v81
	v_cndmask_b32_e32 v69, v72, v73, vcc
	v_max_f32_e32 v69, 0, v69
	v_sqrt_f32_e32 v69, v69
	v_mul_f32_e32 v237, 0xc1000000, v81
	v_add_f32_e32 v97, 1.0, v97
	v_rcp_f32_e32 v97, v97
	v_mul_f32_e32 v93, v248, v69
	v_mul_f32_e32 v69, v200, v65
	v_mul_f32_e32 v72, 0x3fb8aa3b, v69
	v_exp_f32_e32 v96, v72
	v_add_f32_e32 v69, v69, v69
	v_fmamk_f32 v73, v69, 0x3d2aaaab, v196
	v_fma_f32 v73, v69, v73, 0.5
	v_fma_f32 v73, v69, v73, 1.0
	v_fma_f32 v72, -v96, v96, 1.0
	v_mul_f32_e64 v73, v73, -v69
	v_cmp_lt_f32_e32 vcc, s40, v69
	v_pk_mul_f32 v[76:77], v[76:77], s[44:45] op_sel_hi:[1,0]
	v_mov_b32_e32 v160, v171
	v_cndmask_b32_e32 v69, v72, v73, vcc
	v_max_f32_e32 v69, 0, v69
	v_sqrt_f32_e32 v69, v69
	v_mov_b32_e32 v159, v161
	v_mov_b32_e32 v139, v171
	v_mul_f32_e32 v120, 0xbfb8aa3b, v120
	v_mul_f32_e32 v85, v251, v69
	v_mul_f32_e32 v69, v201, v64
	v_mul_f32_e32 v72, 0x3fb8aa3b, v69
	v_exp_f32_e32 v98, v72
	v_add_f32_e32 v69, v69, v69
	v_fmamk_f32 v73, v69, 0x3d2aaaab, v196
	v_fma_f32 v73, v69, v73, 0.5
	v_fma_f32 v73, v69, v73, 1.0
	v_fma_f32 v72, -v98, v98, 1.0
	v_mul_f32_e64 v73, v73, -v69
	v_cmp_lt_f32_e32 vcc, s40, v69
	v_mul_f32_e32 v112, 0xbfb8aa3b, v112
	v_exp_f32_e32 v120, v120
	v_cndmask_b32_e32 v69, v72, v73, vcc
	v_max_f32_e32 v69, 0, v69
	v_sqrt_f32_e32 v69, v69
	v_exp_f32_e32 v112, v112
	v_mul_f32_e32 v121, 0xbfb8aa3b, v121
	v_mul_f32_e32 v113, 0xbfb8aa3b, v113
	v_mul_f32_e32 v89, v252, v69
	v_mul_f32_e32 v69, v206, v65
	v_mul_f32_e32 v72, 0x3fb8aa3b, v69
	v_exp_f32_e32 v84, v72
	v_add_f32_e32 v69, v69, v69
	v_fmamk_f32 v73, v69, 0x3d2aaaab, v196
	v_fma_f32 v73, v69, v73, 0.5
	v_fma_f32 v73, v69, v73, 1.0
	v_fma_f32 v72, -v84, v84, 1.0
	v_mul_f32_e64 v73, v73, -v69
	v_cmp_lt_f32_e32 vcc, s40, v69
	v_add_f32_e32 v120, 1.0, v120
	v_exp_f32_e32 v121, v121
	v_cndmask_b32_e32 v69, v72, v73, vcc
	v_max_f32_e32 v69, 0, v69
	v_sqrt_f32_e32 v69, v69
	v_add_f32_e32 v112, 1.0, v112
	v_exp_f32_e32 v113, v113
	v_rcp_f32_e32 v120, v120
	v_mul_f32_e32 v81, v199, v69
	v_mul_f32_e32 v69, v101, v64
	v_mul_f32_e32 v72, 0x3fb8aa3b, v69
	v_exp_f32_e32 v86, v72
	v_add_f32_e32 v69, v69, v69
	v_fmamk_f32 v73, v69, 0x3d2aaaab, v196
	v_fma_f32 v73, v69, v73, 0.5
	v_fma_f32 v73, v69, v73, 1.0
	v_fma_f32 v72, -v86, v86, 1.0
	v_mul_f32_e64 v73, v73, -v69
	v_cmp_lt_f32_e32 vcc, s40, v69
	v_rcp_f32_e32 v112, v112
	v_add_f32_e32 v121, 1.0, v121
	v_cndmask_b32_e32 v69, v72, v73, vcc
	v_max_f32_e32 v69, 0, v69
	v_sqrt_f32_e32 v69, v69
	v_or_b32_e32 v124, 0x100, v133
	v_add_f32_e32 v113, 1.0, v113
	v_or_b32_e32 v125, 0x200, v133
	v_mul_f32_e32 v87, v97, v69
	v_mul_f32_e32 v69, v80, v65
	v_mul_f32_e32 v72, 0x3fb8aa3b, v69
	v_exp_f32_e32 v80, v72
	v_add_f32_e32 v69, v69, v69
	v_fmamk_f32 v73, v69, 0x3d2aaaab, v196
	v_fma_f32 v73, v69, v73, 0.5
	v_fma_f32 v73, v69, v73, 1.0
	v_fma_f32 v72, -v80, v80, 1.0
	v_mul_f32_e64 v73, v73, -v69
	v_cmp_lt_f32_e32 vcc, s40, v69
	v_rcp_f32_e32 v217, v121
	v_mul_f32_e32 v220, 0xc1000000, v120
	v_cndmask_b32_e32 v69, v72, v73, vcc
	v_max_f32_e32 v69, 0, v69
	v_sqrt_f32_e32 v69, v69
	v_or3_b32 v120, v128, v124, v146
	v_mov_b32_e32 v121, v129
	v_rcp_f32_e32 v221, v113
	v_mul_f32_e32 v75, v99, v69
	v_mul_f32_e32 v69, v207, v64
	v_mul_f32_e32 v72, 0x3fb8aa3b, v69
	v_exp_f32_e32 v82, v72
	v_add_f32_e32 v69, v69, v69
	v_fmamk_f32 v73, v69, 0x3d2aaaab, v196
	v_fma_f32 v73, v69, v73, 0.5
	v_fma_f32 v73, v69, v73, 1.0
	v_fma_f32 v72, -v82, v82, 1.0
	v_mul_f32_e64 v73, v73, -v69
	v_cmp_lt_f32_e32 vcc, s40, v69
	v_mul_f32_e32 v224, 0xc1000000, v112
	v_or3_b32 v112, v128, v125, v146
	v_cndmask_b32_e32 v69, v72, v73, vcc
	v_max_f32_e32 v69, 0, v69
	v_sqrt_f32_e32 v69, v69
	v_pk_mul_f32 v[72:73], v[122:123], s[44:45] op_sel_hi:[1,0]
	v_mov_b32_e32 v113, v129
	v_pk_mul_f32 v[122:123], v[72:73], v[64:65]
	v_mul_f32_e32 v83, v103, v69
	v_mul_f32_e32 v69, 0x3fb8aa3b, v123
	v_exp_f32_e32 v72, v69
	v_pk_add_f32 v[150:151], v[122:123], v[122:123]
	v_pk_mul_f32 v[64:65], v[76:77], v[64:65]
	v_fmamk_f32 v73, v151, 0x3d2aaaab, v196
	v_fma_f32 v73, v151, v73, 0.5
	v_fma_f32 v73, v151, v73, 1.0
	v_fma_f32 v69, -v72, v72, 1.0
	v_mul_f32_e64 v73, v73, -v151
	v_cmp_lt_f32_e64 s[0:1], s40, v151
	v_fmamk_f32 v78, v150, 0x3d2aaaab, v196
	v_fma_f32 v78, v150, v78, 0.5
	v_cndmask_b32_e64 v69, v69, v73, s[0:1]
	v_max_f32_e32 v69, 0, v69
	v_sqrt_f32_e32 v69, v69
	v_fma_f32 v78, v150, v78, 1.0
	v_cmp_lt_f32_e32 vcc, s40, v150
	v_mul_f32_e64 v78, v78, -v150
	v_mul_f32_e32 v73, v203, v69
	v_mul_f32_e32 v69, 0x3fb8aa3b, v122
	v_exp_f32_e32 v74, v69
	v_pk_add_f32 v[122:123], v[64:65], v[64:65]
	v_mul_f32_e32 v64, 0x3fb8aa3b, v64
	v_cmp_lt_f32_e64 s[0:1], s40, v123
	v_fma_f32 v69, -v74, v74, 1.0
	v_cndmask_b32_e32 v69, v69, v78, vcc
	v_max_f32_e32 v69, 0, v69
	v_sqrt_f32_e32 v69, v69
	v_exp_f32_e32 v78, v64
	v_cmp_lt_f32_e32 vcc, s40, v122
	v_lshl_add_u64 v[120:121], v[120:121], 3, s[14:15]
	v_mul_f32_e32 v88, v208, v69
	v_mul_f32_e32 v69, 0x3fb8aa3b, v65
	v_exp_f32_e32 v76, v69
	v_fmamk_f32 v65, v123, 0x3d2aaaab, v196
	v_fma_f32 v65, v123, v65, 0.5
	v_fma_f32 v65, v123, v65, 1.0
	v_fma_f32 v69, -v76, v76, 1.0
	v_mul_f32_e64 v65, v65, -v123
	v_cndmask_b32_e64 v65, v69, v65, s[0:1]
	v_max_f32_e32 v65, 0, v65
	v_sqrt_f32_e32 v65, v65
	v_fma_f32 v64, -v78, v78, 1.0
	v_cmp_lt_f32_e64 s[0:1], |v145|, s39
	v_lshl_add_u64 v[112:113], v[112:113], 3, s[14:15]
	v_mul_f32_e32 v69, v68, v65
	v_fmamk_f32 v65, v122, 0x3d2aaaab, v196
	v_fma_f32 v65, v122, v65, 0.5
	v_fma_f32 v65, v122, v65, 1.0
	v_mul_f32_e64 v65, v65, -v122
	v_cndmask_b32_e32 v64, v64, v65, vcc
	v_max_f32_e32 v64, 0, v64
	v_sqrt_f32_e32 v64, v64
	v_cmp_neq_f32_e32 vcc, s27, v178
	v_mul_f32_e32 v68, v189, v64
	v_add_f32_e32 v64, v66, v90
	v_mul_f32_e32 v64, 0xbfb8aa3b, v64
	v_exp_f32_e32 v64, v64
	v_add_f32_e32 v66, v70, v94
	v_mov_b32_e32 v90, v169
	v_add_f32_e32 v64, 1.0, v64
	v_rcp_f32_e32 v65, v64
	v_mul_f32_e32 v64, 0xbfb8aa3b, v66
	v_add_f32_e32 v66, v71, v95
	v_mul_f32_e32 v66, 0xbfb8aa3b, v66
	v_exp_f32_e32 v64, v64
	v_exp_f32_e32 v66, v66
	v_add_f32_e32 v64, 1.0, v64
	v_add_f32_e32 v66, 1.0, v66
	v_rcp_f32_e32 v70, v64
	v_add_f32_e32 v64, v67, v91
	v_rcp_f32_e32 v71, v66
	v_mov_b32_e32 v66, v168
	v_mov_b32_e32 v67, v164
	v_mov_b32_e32 v91, v165
	v_pk_add_f32 v[90:91], v[66:67], v[90:91]
	v_mul_f32_e32 v64, 0xbfb8aa3b, v64
	v_pk_add_f32 v[94:95], v[160:161], v[90:91]
	v_mov_b32_e32 v163, v91
	v_mov_b32_e32 v165, v95
	v_mov_b32_e32 v169, v94
	v_pk_add_f32 v[122:123], v[164:165], v[158:159] neg_lo:[0,1] neg_hi:[0,1]
	v_pk_add_f32 v[152:153], v[168:169], v[138:139] neg_lo:[0,1] neg_hi:[0,1]
	v_mov_b32_e32 v155, v122
	v_mov_b32_e32 v154, v152
	v_mov_b32_e32 v167, v90
	v_pk_add_f32 v[150:151], v[162:163], v[122:123] neg_lo:[0,1] neg_hi:[0,1]
	v_pk_add_f32 v[66:67], v[66:67], v[154:155] neg_lo:[0,1] neg_hi:[0,1]
	v_mov_b32_e32 v139, v158
	v_pk_add_f32 v[90:91], v[166:167], v[152:153] neg_lo:[0,1] neg_hi:[0,1]
	v_pk_add_f32 v[66:67], v[138:139], v[66:67] neg_lo:[0,1] neg_hi:[0,1]
	v_mov_b32_e32 v122, v90
	v_mov_b32_e32 v123, v150
	v_pk_add_f32 v[66:67], v[122:123], v[66:67]
	v_mov_b32_e32 v150, v91
	v_pk_add_f32 v[66:67], v[66:67], v[150:151]
	v_exp_f32_e32 v64, v64
	v_pk_add_f32 v[66:67], v[94:95], v[66:67]
	v_add_f32_e32 v64, 1.0, v64
	v_cndmask_b32_e32 v66, v209, v66, vcc
	v_cmp_neq_f32_e32 vcc, s27, v145
	v_rcp_f32_e32 v64, v64
	s_nop 0
	v_cndmask_b32_e32 v67, v209, v67, vcc
	v_cndmask_b32_e64 v67, v67, v145, s[0:1]
	v_mul_f32_e32 v77, v215, v67
	v_mul_f32_e32 v90, 0x3fb8aa3b, v77
	v_exp_f32_e32 v150, v90
	v_add_f32_e32 v77, v77, v77
	v_fmamk_f32 v91, v77, 0x3d2aaaab, v196
	v_fma_f32 v91, v77, v91, 0.5
	v_cmp_lt_f32_e64 vcc, |v178|, s39
	v_fma_f32 v91, v77, v91, 1.0
	v_fma_f32 v90, -v150, v150, 1.0
	v_cndmask_b32_e32 v66, v66, v178, vcc
	v_mul_f32_e64 v91, v91, -v77
	v_cmp_lt_f32_e32 vcc, s40, v77
	s_nop 1
	v_cndmask_b32_e32 v77, v90, v91, vcc
	v_max_f32_e32 v77, 0, v77
	v_sqrt_f32_e32 v77, v77
	s_nop 0
	v_mul_f32_e32 v77, v214, v77
	v_mul_f32_e32 v151, v77, v170
	v_mul_f32_e32 v77, v216, v66
	v_mul_f32_e32 v90, 0x3fb8aa3b, v77
	v_exp_f32_e32 v152, v90
	v_add_f32_e32 v77, v77, v77
	v_fmamk_f32 v91, v77, 0x3d2aaaab, v196
	v_fma_f32 v91, v77, v91, 0.5
	v_fma_f32 v91, v77, v91, 1.0
	v_fma_f32 v90, -v152, v152, 1.0
	v_mul_f32_e64 v91, v91, -v77
	v_cmp_lt_f32_e32 vcc, s40, v77
	s_nop 1
	v_cndmask_b32_e32 v77, v90, v91, vcc
	v_max_f32_e32 v77, 0, v77
	v_sqrt_f32_e32 v77, v77
	s_nop 0
	v_mul_f32_e32 v77, v183, v77
	v_mul_f32_e32 v153, v77, v149
	global_store_dwordx4 v[130:131], v[150:153], off offset:16
	v_add_co_u32_e32 v90, vcc, s66, v136
	v_mul_f32_e32 v77, v219, v67
	s_nop 0
	v_addc_co_u32_e32 v91, vcc, 0, v137, vcc
	global_load_dwordx2 v[90:91], v[90:91], off
	v_mul_f32_e32 v94, 0x3fb8aa3b, v77
	v_exp_f32_e32 v150, v94
	v_add_f32_e32 v77, v77, v77
	v_fmamk_f32 v95, v77, 0x3d2aaaab, v196
	v_fma_f32 v95, v77, v95, 0.5
	v_fma_f32 v95, v77, v95, 1.0
	v_fma_f32 v94, -v150, v150, 1.0
	v_mul_f32_e64 v95, v95, -v77
	v_cmp_lt_f32_e32 vcc, s40, v77
	s_nop 1
	v_cndmask_b32_e32 v77, v94, v95, vcc
	v_max_f32_e32 v77, 0, v77
	v_sqrt_f32_e32 v77, v77
	s_nop 0
	v_mul_f32_e32 v77, v218, v77
	v_mul_f32_e32 v151, v77, v182
	v_mul_f32_e32 v77, v220, v66
	v_mul_f32_e32 v94, 0x3fb8aa3b, v77
	v_exp_f32_e32 v152, v94
	v_add_f32_e32 v77, v77, v77
	v_fmamk_f32 v95, v77, 0x3d2aaaab, v196
	v_fma_f32 v95, v77, v95, 0.5
	v_fma_f32 v95, v77, v95, 1.0
	v_fma_f32 v94, -v152, v152, 1.0
	v_mul_f32_e64 v95, v95, -v77
	v_cmp_lt_f32_e32 vcc, s40, v77
	s_nop 1
	v_cndmask_b32_e32 v77, v94, v95, vcc
	v_max_f32_e32 v77, 0, v77
	v_sqrt_f32_e32 v77, v77
	s_nop 0
	v_mul_f32_e32 v77, v217, v77
	v_mul_f32_e32 v153, v77, v172
	global_store_dwordx4 v[120:121], v[104:107], off
	global_store_dwordx4 v[120:121], v[150:153], off offset:16
	v_add_co_u32_e32 v94, vcc, s67, v136
	s_waitcnt vmcnt(2)
	v_lshlrev_b32_e32 v77, 16, v90
	v_addc_co_u32_e32 v95, vcc, 0, v137, vcc
	global_load_dwordx2 v[94:95], v[94:95], off
	v_and_b32_e32 v90, 0xffff0000, v90
	v_mul_f32_e32 v101, v92, v77
	v_mul_f32_e32 v77, v223, v67
	v_mul_f32_e32 v103, v93, v90
	v_mul_f32_e32 v90, 0x3fb8aa3b, v77
	v_exp_f32_e32 v90, v90
	v_add_f32_e32 v77, v77, v77
	v_fmamk_f32 v92, v77, 0x3d2aaaab, v196
	v_fma_f32 v92, v77, v92, 0.5
	v_fma_f32 v92, v77, v92, 1.0
	v_lshlrev_b32_e32 v97, 16, v91
	v_and_b32_e32 v99, 0xffff0000, v91
	v_fma_f32 v91, -v90, v90, 1.0
	v_mul_f32_e64 v92, v92, -v77
	v_cmp_lt_f32_e32 vcc, s40, v77
	s_nop 1
	v_cndmask_b32_e32 v77, v91, v92, vcc
	v_max_f32_e32 v77, 0, v77
	v_sqrt_f32_e32 v77, v77
	s_nop 0
	v_mul_f32_e32 v77, v222, v77
	v_mul_f32_e32 v91, v77, v97
	v_mul_f32_e32 v77, v224, v66
	v_mul_f32_e32 v92, 0x3fb8aa3b, v77
	v_exp_f32_e32 v92, v92
	v_add_f32_e32 v77, v77, v77
	v_fmamk_f32 v97, v77, 0x3d2aaaab, v196
	v_fma_f32 v97, v77, v97, 0.5
	v_fma_f32 v97, v77, v97, 1.0
	v_fma_f32 v93, -v92, v92, 1.0
	v_mul_f32_e64 v97, v97, -v77
	v_cmp_lt_f32_e32 vcc, s40, v77
	s_nop 1
	v_cndmask_b32_e32 v77, v93, v97, vcc
	v_max_f32_e32 v77, 0, v77
	v_sqrt_f32_e32 v77, v77
	s_nop 0
	v_mul_f32_e32 v77, v221, v77
	v_mul_f32_e32 v93, v77, v99
	global_store_dwordx4 v[112:113], v[100:103], off
	global_store_dwordx4 v[112:113], v[90:93], off offset:16
	s_mov_b32 s22, 0x40000
	s_nop 0
	v_add_co_u32_e32 v90, vcc, s22, v136
	s_waitcnt vmcnt(2)
	v_lshlrev_b32_e32 v77, 16, v94
	v_addc_co_u32_e32 v91, vcc, 0, v137, vcc
	global_load_dwordx2 v[100:101], v[90:91], off
	v_mul_f32_e32 v97, v85, v77
	v_mul_f32_e32 v77, v227, v67
	v_and_b32_e32 v90, 0xffff0000, v94
	v_mul_f32_e32 v85, 0x3fb8aa3b, v77
	v_mul_f32_e32 v99, v89, v90
	v_exp_f32_e32 v90, v85
	v_add_f32_e32 v77, v77, v77
	v_fmamk_f32 v89, v77, 0x3d2aaaab, v196
	v_fma_f32 v89, v77, v89, 0.5
	v_fma_f32 v89, v77, v89, 1.0
	v_fma_f32 v85, -v90, v90, 1.0
	v_mul_f32_e64 v89, v89, -v77
	v_cmp_lt_f32_e32 vcc, s40, v77
	v_lshlrev_b32_e32 v91, 16, v95
	v_and_b32_e32 v93, 0xffff0000, v95
	v_cndmask_b32_e32 v77, v85, v89, vcc
	v_max_f32_e32 v77, 0, v77
	v_sqrt_f32_e32 v77, v77
	s_nop 0
	v_mul_f32_e32 v77, v226, v77
	v_mul_f32_e32 v91, v77, v91
	v_mul_f32_e32 v77, v228, v66
	v_mul_f32_e32 v85, 0x3fb8aa3b, v77
	v_exp_f32_e32 v92, v85
	v_add_f32_e32 v77, v77, v77
	v_fmamk_f32 v89, v77, 0x3d2aaaab, v196
	v_fma_f32 v89, v77, v89, 0.5
	v_fma_f32 v89, v77, v89, 1.0
	v_fma_f32 v85, -v92, v92, 1.0
	v_mul_f32_e64 v89, v89, -v77
	v_cmp_lt_f32_e32 vcc, s40, v77
	s_nop 1
	v_cndmask_b32_e32 v77, v85, v89, vcc
	v_max_f32_e32 v77, 0, v77
	v_sqrt_f32_e32 v77, v77
	s_nop 0
	v_mul_f32_e32 v77, v225, v77
	v_mul_f32_e32 v93, v77, v93
	global_store_dwordx4 v[108:109], v[96:99], off
	global_store_dwordx4 v[108:109], v[90:93], off offset:16
	s_mov_b32 s41, 0x50000
	s_nop 0
	v_add_co_u32_e32 v90, vcc, s41, v136
	s_waitcnt vmcnt(2)
	v_lshlrev_b32_e32 v77, 16, v100
	v_addc_co_u32_e32 v91, vcc, 0, v137, vcc
	global_load_dwordx2 v[94:95], v[90:91], off
	v_mul_f32_e32 v85, v81, v77
	v_mul_f32_e32 v77, v231, v67
	v_mul_f32_e32 v81, 0x3fb8aa3b, v77
	v_and_b32_e32 v89, 0xffff0000, v100
	v_exp_f32_e32 v90, v81
	v_add_f32_e32 v77, v77, v77
	v_mul_f32_e32 v87, v87, v89
	v_fmamk_f32 v89, v77, 0x3d2aaaab, v196
	v_fma_f32 v89, v77, v89, 0.5
	v_fma_f32 v89, v77, v89, 1.0
	v_fma_f32 v81, -v90, v90, 1.0
	v_mul_f32_e64 v89, v89, -v77
	v_cmp_lt_f32_e32 vcc, s40, v77
	v_lshlrev_b32_e32 v91, 16, v101
	v_and_b32_e32 v93, 0xffff0000, v101
	v_cndmask_b32_e32 v77, v81, v89, vcc
	v_max_f32_e32 v77, 0, v77
	v_sqrt_f32_e32 v77, v77
	s_nop 0
	v_mul_f32_e32 v77, v230, v77
	v_mul_f32_e32 v91, v77, v91
	v_mul_f32_e32 v77, v232, v66
	v_mul_f32_e32 v81, 0x3fb8aa3b, v77
	v_exp_f32_e32 v92, v81
	v_add_f32_e32 v77, v77, v77
	v_fmamk_f32 v89, v77, 0x3d2aaaab, v196
	v_fma_f32 v89, v77, v89, 0.5
	v_fma_f32 v89, v77, v89, 1.0
	v_fma_f32 v81, -v92, v92, 1.0
	v_mul_f32_e64 v89, v89, -v77
	v_cmp_lt_f32_e32 vcc, s40, v77
	s_nop 1
	v_cndmask_b32_e32 v77, v81, v89, vcc
	v_max_f32_e32 v77, 0, v77
	v_sqrt_f32_e32 v77, v77
	s_nop 0
	v_mul_f32_e32 v77, v229, v77
	v_mul_f32_e32 v93, v77, v93
	global_store_dwordx4 v[110:111], v[84:87], off
	global_store_dwordx4 v[110:111], v[90:93], off offset:16
	s_mov_b32 s23, 0x60000
	v_add_co_u32_e32 v84, vcc, s23, v136
	s_waitcnt vmcnt(2)
	v_lshlrev_b32_e32 v77, 16, v94
	v_addc_co_u32_e32 v85, vcc, 0, v137, vcc
	global_load_dwordx2 v[90:91], v[84:85], off
	v_mul_f32_e32 v81, v75, v77
	v_mul_f32_e32 v75, v235, v67
	v_and_b32_e32 v84, 0xffff0000, v94
	v_mul_f32_e32 v77, 0x3fb8aa3b, v75
	v_mul_f32_e32 v83, v83, v84
	v_exp_f32_e32 v84, v77
	v_add_f32_e32 v75, v75, v75
	v_fmamk_f32 v86, v75, 0x3d2aaaab, v196
	v_fma_f32 v86, v75, v86, 0.5
	v_fma_f32 v86, v75, v86, 1.0
	v_fma_f32 v77, -v84, v84, 1.0
	v_mul_f32_e64 v86, v86, -v75
	v_cmp_lt_f32_e32 vcc, s40, v75
	v_lshlrev_b32_e32 v85, 16, v95
	v_and_b32_e32 v87, 0xffff0000, v95
	v_cndmask_b32_e32 v75, v77, v86, vcc
	v_max_f32_e32 v75, 0, v75
	v_sqrt_f32_e32 v75, v75
	s_nop 0
	v_mul_f32_e32 v75, v234, v75
	v_mul_f32_e32 v85, v75, v85
	v_mul_f32_e32 v75, v237, v66
	v_mul_f32_e32 v77, 0x3fb8aa3b, v75
	v_exp_f32_e32 v86, v77
	v_add_f32_e32 v75, v75, v75
	v_fmamk_f32 v89, v75, 0x3d2aaaab, v196
	v_fma_f32 v89, v75, v89, 0.5
	v_fma_f32 v89, v75, v89, 1.0
	v_fma_f32 v77, -v86, v86, 1.0
	v_mul_f32_e64 v89, v89, -v75
	v_cmp_lt_f32_e32 vcc, s40, v75
	s_nop 1
	v_cndmask_b32_e32 v75, v77, v89, vcc
	v_max_f32_e32 v75, 0, v75
	v_sqrt_f32_e32 v75, v75
	s_nop 0
	v_mul_f32_e32 v75, v233, v75
	v_mul_f32_e32 v87, v75, v87
	global_store_dwordx4 v[114:115], v[80:83], off
	global_store_dwordx4 v[114:115], v[84:87], off offset:16
	s_mov_b32 s42, 0x70000
	v_add_co_u32_e32 v80, vcc, s42, v136
	s_waitcnt vmcnt(2)
	v_lshlrev_b32_e32 v75, 16, v90
	v_addc_co_u32_e32 v81, vcc, 0, v137, vcc
	global_load_dwordx2 v[84:85], v[80:81], off
	v_pk_mul_f32 v[80:81], v[118:119], s[44:45] op_sel_hi:[1,0]
	v_and_b32_e32 v77, 0xffff0000, v90
	v_pk_mul_f32 v[82:83], v[80:81], v[66:67]
	v_mul_f32_e32 v73, v73, v75
	v_mul_f32_e32 v75, v88, v77
	v_mul_f32_e32 v77, 0x3fb8aa3b, v83
	v_exp_f32_e32 v80, v77
	v_pk_add_f32 v[86:87], v[82:83], v[82:83]
	v_lshlrev_b32_e32 v89, 16, v91
	v_fmamk_f32 v81, v87, 0x3d2aaaab, v196
	v_fma_f32 v81, v87, v81, 0.5
	v_fma_f32 v81, v87, v81, 1.0
	v_fma_f32 v77, -v80, v80, 1.0
	v_mul_f32_e64 v81, v81, -v87
	v_cmp_lt_f32_e64 s[0:1], s40, v87
	v_fmamk_f32 v83, v86, 0x3d2aaaab, v196
	v_fma_f32 v83, v86, v83, 0.5
	v_cndmask_b32_e64 v77, v77, v81, s[0:1]
	v_max_f32_e32 v77, 0, v77
	v_sqrt_f32_e32 v77, v77
	v_fma_f32 v83, v86, v83, 1.0
	v_cmp_lt_f32_e32 vcc, s40, v86
	v_mul_f32_e64 v83, v83, -v86
	v_mul_f32_e32 v77, v236, v77
	v_mul_f32_e32 v81, v77, v89
	v_mul_f32_e32 v77, 0x3fb8aa3b, v82
	v_exp_f32_e32 v82, v77
	v_and_b32_e32 v90, 0xffff0000, v91
	v_fma_f32 v77, -v82, v82, 1.0
	v_cndmask_b32_e32 v77, v77, v83, vcc
	v_max_f32_e32 v77, 0, v77
	v_sqrt_f32_e32 v77, v77
	s_nop 0
	v_mul_f32_e32 v77, v79, v77
	v_mul_f32_e32 v83, v77, v90
	global_store_dwordx4 v[116:117], v[72:75], off
	global_store_dwordx4 v[116:117], v[80:83], off offset:16
	v_pk_mul_f32 v[64:65], v[64:65], s[44:45] op_sel_hi:[1,0]
	s_waitcnt vmcnt(2)
	v_lshlrev_b32_e32 v72, 16, v84
	v_pk_mul_f32 v[66:67], v[64:65], v[66:67]
	v_mul_f32_e32 v77, v69, v72
	v_pk_add_f32 v[72:73], v[66:67], v[66:67]
	v_mul_f32_e32 v64, 0x3fb8aa3b, v67
	v_fmamk_f32 v67, v73, 0x3d2aaaab, v196
	v_exp_f32_e32 v64, v64
	v_fma_f32 v67, v73, v67, 0.5
	v_mul_f32_e32 v66, 0x3fb8aa3b, v66
	v_fma_f32 v67, v73, v67, 1.0
	v_exp_f32_e32 v66, v66
	v_mul_f32_e64 v67, v67, -v73
	v_cmp_lt_f32_e32 vcc, s40, v73
	v_fmamk_f32 v73, v72, 0x3d2aaaab, v196
	v_fma_f32 v73, v72, v73, 0.5
	v_fma_f32 v69, -v64, v64, 1.0
	v_fma_f32 v73, v72, v73, 1.0
	v_cndmask_b32_e32 v67, v69, v67, vcc
	v_fma_f32 v69, -v66, v66, 1.0
	v_mul_f32_e64 v73, v73, -v72
	v_cmp_lt_f32_e32 vcc, s40, v72
	v_max_f32_e32 v67, 0, v67
	v_sqrt_f32_e32 v67, v67
	v_cndmask_b32_e32 v69, v69, v73, vcc
	v_max_f32_e32 v69, 0, v69
	v_sqrt_f32_e32 v69, v69
	v_or_b32_e32 v122, 0x700, v133
	v_and_b32_e32 v74, 0xffff0000, v84
	v_lshlrev_b32_e32 v65, 16, v85
	v_mul_f32_e32 v67, v70, v67
	v_or3_b32 v128, v128, v122, v146
	v_and_b32_e32 v75, 0xffff0000, v85
	v_mul_f32_e32 v79, v68, v74
	v_mul_f32_e32 v65, v67, v65
	v_mul_f32_e32 v67, v71, v69
	v_lshl_add_u64 v[68:69], v[128:129], 3, s[14:15]
	v_mul_f32_e32 v67, v67, v75
	global_store_dwordx4 v[68:69], v[76:79], off
	global_store_dwordx4 v[68:69], v[64:67], off offset:16
	v_ashrrev_i32_e32 v143, 31, v142
	v_lshl_add_u64 v[106:107], v[142:143], 0, v[146:147]
	v_lshlrev_b64 v[68:69], 2, v[106:107]
	v_lshl_add_u64 v[64:65], s[4:5], 0, v[68:69]
	global_load_dwordx4 v[72:75], v[64:65], off offset:64
	v_lshl_add_u64 v[64:65], s[6:7], 0, v[68:69]
	v_lshl_add_u64 v[68:69], s[8:9], 0, v[68:69]
	global_load_dwordx4 v[68:71], v[68:69], off offset:64
	v_or_b32_e32 v108, 16, v142
	global_load_dwordx4 v[64:67], v[64:65], off offset:64
	s_waitcnt vmcnt(2)
	v_mul_f32_e32 v76, 0xbfb8aa3b, v72
	v_fma_f32 v77, v72, s24, -v76
	v_rndne_f32_e32 v78, v76
	v_fmac_f32_e32 v77, 0xb2a5705f, v72
	v_sub_f32_e32 v76, v76, v78
	v_add_f32_e32 v76, v76, v77
	v_exp_f32_e32 v76, v76
	v_cvt_i32_f32_e32 v77, v78
	v_cmp_nlt_f32_e32 vcc, s25, v72
	s_waitcnt vmcnt(1)
	v_add_f32_e32 v56, v56, v68
	v_mul_f32_e32 v56, 0xbfb8aa3b, v56
	v_ldexp_f32 v76, v76, v77
	v_cndmask_b32_e32 v76, 0, v76, vcc
	v_cmp_ngt_f32_e32 vcc, s26, v72
	v_exp_f32_e32 v56, v56
	v_add_f32_e32 v57, v57, v69
	v_cndmask_b32_e32 v123, v209, v76, vcc
	v_add_f32_e32 v72, 1.0, v123
	v_add_f32_e32 v76, -1.0, v72
	v_sub_f32_e32 v77, v76, v72
	v_add_f32_e32 v77, 1.0, v77
	v_sub_f32_e32 v76, v123, v76
	v_add_f32_e32 v78, v76, v77
	v_frexp_mant_f32_e32 v76, v72
	v_cmp_gt_f32_e32 vcc, s37, v76
	v_cvt_f64_f32_e32 v[76:77], v72
	v_frexp_exp_i32_f64_e32 v76, v[76:77]
	v_subbrev_co_u32_e32 v84, vcc, 0, v76, vcc
	v_sub_u32_e32 v76, 0, v84
	v_ldexp_f32 v72, v72, v76
	v_ldexp_f32 v76, v78, v76
	v_add_f32_e32 v78, -1.0, v72
	v_add_f32_e32 v77, 1.0, v78
	v_sub_f32_e32 v77, v72, v77
	v_add_f32_e32 v79, v76, v77
	v_add_f32_e32 v77, v78, v79
	v_sub_f32_e32 v78, v78, v77
	v_add_f32_e32 v85, v79, v78
	v_add_f32_e32 v78, 1.0, v72
	v_add_f32_e32 v79, -1.0, v78
	v_sub_f32_e32 v72, v72, v79
	v_add_f32_e32 v72, v76, v72
	v_add_f32_e32 v86, v78, v72
	v_rcp_f32_e32 v87, v86
	v_sub_f32_e32 v76, v78, v86
	v_add_f32_e32 v72, v72, v76
	v_cmp_nlt_f32_e32 vcc, s25, v73
	v_mul_f32_e32 v88, v77, v87
	v_mul_f32_e32 v78, v86, v88
	v_fma_f32 v80, v88, v86, -v78
	v_fmac_f32_e32 v80, v88, v72
	v_add_f32_e32 v76, v78, v80
	v_sub_f32_e32 v79, v77, v76
	v_pk_add_f32 v[82:83], v[76:77], v[78:79] neg_lo:[0,1] neg_hi:[0,1]
	v_mov_b32_e32 v81, v76
	v_pk_add_f32 v[76:77], v[82:83], v[80:81] neg_lo:[0,1] neg_hi:[0,1]
	v_add_f32_e32 v56, 1.0, v56
	v_add_f32_e32 v77, v85, v77
	v_add_f32_e32 v76, v76, v77
	v_add_f32_e32 v77, v79, v76
	v_mul_f32_e32 v85, v87, v77
	v_mul_f32_e32 v78, v86, v85
	v_fma_f32 v80, v85, v86, -v78
	v_fmac_f32_e32 v80, v85, v72
	v_sub_f32_e32 v72, v79, v77
	v_add_f32_e32 v72, v76, v72
	v_add_f32_e32 v76, v78, v80
	v_sub_f32_e32 v79, v77, v76
	v_pk_add_f32 v[82:83], v[76:77], v[78:79] neg_lo:[0,1] neg_hi:[0,1]
	v_mov_b32_e32 v81, v76
	v_pk_add_f32 v[76:77], v[82:83], v[80:81] neg_lo:[0,1] neg_hi:[0,1]
	v_rcp_f32_e32 v145, v56
	v_add_f32_e32 v72, v72, v77
	v_add_f32_e32 v72, v76, v72
	v_add_f32_e32 v77, v88, v85
	v_add_f32_e32 v72, v79, v72
	v_sub_f32_e32 v76, v77, v88
	v_mul_f32_e32 v72, v87, v72
	v_sub_f32_e32 v76, v85, v76
	v_add_f32_e32 v72, v76, v72
	v_add_f32_e32 v78, v77, v72
	v_mul_f32_e32 v80, v78, v78
	v_fmamk_f32 v76, v80, 0x3e9b6dac, v195
	v_fmaak_f32 v149, v80, v76, 0x3f2aaada
	v_cvt_f32_i32_e32 v76, v84
	v_sub_f32_e32 v77, v78, v77
	v_sub_f32_e32 v72, v72, v77
	v_mul_f32_e32 v77, v78, v80
	v_pk_mul_f32 v[80:81], v[76:77], v[148:149]
	v_ldexp_f32 v79, v78, 1
	v_fma_f32 v78, v76, s38, -v80
	v_fmac_f32_e32 v78, 0xb102e308, v76
	v_pk_add_f32 v[82:83], v[80:81], v[78:79]
	v_ldexp_f32 v72, v72, 1
	v_sub_f32_e32 v76, v83, v79
	v_sub_f32_e32 v76, v81, v76
	v_add_f32_e32 v85, v72, v76
	v_mov_b32_e32 v84, v80
	v_pk_add_f32 v[80:81], v[82:83], v[80:81] neg_lo:[0,1] neg_hi:[0,1]
	v_pk_add_f32 v[86:87], v[82:83], v[84:85]
	v_mov_b32_e32 v79, v82
	v_mov_b32_e32 v81, v87
	v_pk_add_f32 v[76:77], v[78:79], v[80:81] neg_lo:[0,1] neg_hi:[0,1]
	v_pk_add_f32 v[78:79], v[78:79], v[80:81]
	v_mov_b32_e32 v84, v85
	v_pk_add_f32 v[80:81], v[78:79], v[82:83] op_sel:[1,0] op_sel_hi:[0,1] neg_lo:[0,1] neg_hi:[0,1]
	v_pk_add_f32 v[88:89], v[86:87], v[80:81] op_sel_hi:[1,0] neg_lo:[0,1] neg_hi:[0,1]
	v_mov_b32_e32 v78, v87
	v_pk_mov_b32 v[80:81], v[82:83], v[80:81] op_sel:[1,0]
	v_mov_b32_e32 v85, v82
	v_pk_add_f32 v[80:81], v[78:79], v[80:81] neg_lo:[0,1] neg_hi:[0,1]
	v_mov_b32_e32 v88, v76
	v_pk_add_f32 v[80:81], v[84:85], v[80:81] neg_lo:[0,1] neg_hi:[0,1]
	v_mul_f32_e32 v72, 0xbfb8aa3b, v73
	v_pk_add_f32 v[82:83], v[88:89], v[80:81]
	v_fma_f32 v78, v73, s24, -v72
	v_rndne_f32_e32 v81, v72
	v_fmac_f32_e32 v78, 0xb2a5705f, v73
	v_sub_f32_e32 v72, v72, v81
	v_add_f32_e32 v72, v72, v78
	v_exp_f32_e32 v72, v72
	v_cvt_i32_f32_e32 v78, v81
	s_waitcnt vmcnt(0)
	v_add_f32_e32 v56, v61, v65
	v_mul_f32_e32 v56, 0xbfb8aa3b, v56
	v_exp_f32_e32 v56, v56
	v_ldexp_f32 v72, v72, v78
	v_cndmask_b32_e32 v72, 0, v72, vcc
	v_cmp_ngt_f32_e32 vcc, s26, v73
	v_add_f32_e32 v56, 1.0, v56
	v_add_f32_e32 v48, v48, v68
	v_cndmask_b32_e32 v129, v209, v72, vcc
	v_add_f32_e32 v78, 1.0, v129
	v_add_f32_e32 v72, -1.0, v78
	v_sub_f32_e32 v73, v72, v78
	v_add_f32_e32 v73, 1.0, v73
	v_sub_f32_e32 v72, v129, v72
	v_add_f32_e32 v81, v72, v73
	v_frexp_mant_f32_e32 v72, v78
	v_cmp_gt_f32_e32 vcc, s37, v72
	v_cvt_f64_f32_e32 v[72:73], v78
	v_frexp_exp_i32_f64_e32 v72, v[72:73]
	v_subbrev_co_u32_e32 v90, vcc, 0, v72, vcc
	v_sub_u32_e32 v72, 0, v90
	v_ldexp_f32 v78, v78, v72
	v_ldexp_f32 v72, v81, v72
	v_add_f32_e32 v81, -1.0, v78
	v_add_f32_e32 v73, 1.0, v81
	v_sub_f32_e32 v73, v78, v73
	v_add_f32_e32 v84, v72, v73
	v_add_f32_e32 v73, v81, v84
	v_sub_f32_e32 v81, v81, v73
	v_add_f32_e32 v81, v84, v81
	v_add_f32_e32 v84, 1.0, v78
	v_add_f32_e32 v85, -1.0, v84
	v_sub_f32_e32 v78, v78, v85
	v_add_f32_e32 v72, v72, v78
	v_add_f32_e32 v78, v84, v72
	v_rcp_f32_e32 v92, v78
	v_sub_f32_e32 v84, v84, v78
	v_add_f32_e32 v91, v72, v84
	v_cmp_nlt_f32_e32 vcc, s25, v74
	v_mul_f32_e32 v93, v73, v92
	v_mul_f32_e32 v84, v78, v93
	v_fma_f32 v86, v93, v78, -v84
	v_fmac_f32_e32 v86, v93, v91
	v_add_f32_e32 v72, v84, v86
	v_sub_f32_e32 v85, v73, v72
	v_pk_add_f32 v[88:89], v[72:73], v[84:85] neg_lo:[0,1] neg_hi:[0,1]
	v_mov_b32_e32 v87, v72
	v_pk_add_f32 v[72:73], v[88:89], v[86:87] neg_lo:[0,1] neg_hi:[0,1]
	v_mul_f32_e32 v48, 0xbfb8aa3b, v48
	v_add_f32_e32 v73, v81, v73
	v_add_f32_e32 v72, v72, v73
	v_add_f32_e32 v73, v85, v72
	v_mul_f32_e32 v81, v92, v73
	v_mul_f32_e32 v84, v78, v81
	v_fma_f32 v86, v81, v78, -v84
	v_fmac_f32_e32 v86, v81, v91
	v_sub_f32_e32 v78, v85, v73
	v_add_f32_e32 v78, v72, v78
	v_add_f32_e32 v72, v84, v86
	v_sub_f32_e32 v85, v73, v72
	v_pk_add_f32 v[88:89], v[72:73], v[84:85] neg_lo:[0,1] neg_hi:[0,1]
	v_mov_b32_e32 v87, v72
	v_pk_add_f32 v[72:73], v[88:89], v[86:87] neg_lo:[0,1] neg_hi:[0,1]
	v_exp_f32_e32 v48, v48
	v_add_f32_e32 v73, v78, v73
	v_add_f32_e32 v72, v72, v73
	v_add_f32_e32 v73, v93, v81
	v_add_f32_e32 v72, v85, v72
	v_sub_f32_e32 v78, v73, v93
	v_mul_f32_e32 v72, v92, v72
	v_sub_f32_e32 v78, v81, v78
	v_add_f32_e32 v78, v78, v72
	v_add_f32_e32 v81, v73, v78
	v_mul_f32_e32 v84, v81, v81
	v_fmamk_f32 v72, v84, 0x3e9b6dac, v195
	v_fmaak_f32 v149, v84, v72, 0x3f2aaada
	v_cvt_f32_i32_e32 v72, v90
	v_sub_f32_e32 v73, v81, v73
	v_sub_f32_e32 v73, v78, v73
	v_ldexp_f32 v78, v73, 1
	v_mul_f32_e32 v73, v81, v84
	v_pk_mul_f32 v[86:87], v[72:73], v[148:149]
	v_ldexp_f32 v85, v81, 1
	v_fma_f32 v84, v72, s38, -v86
	v_fmac_f32_e32 v84, 0xb102e308, v72
	v_pk_add_f32 v[72:73], v[86:87], v[84:85]
	v_mov_b32_e32 v88, v86
	v_sub_f32_e32 v81, v73, v85
	v_sub_f32_e32 v81, v87, v81
	v_add_f32_e32 v89, v78, v81
	v_pk_add_f32 v[86:87], v[72:73], v[86:87] neg_lo:[0,1] neg_hi:[0,1]
	v_pk_add_f32 v[90:91], v[72:73], v[88:89]
	v_mov_b32_e32 v85, v72
	v_mov_b32_e32 v87, v91
	v_pk_add_f32 v[102:103], v[84:85], v[86:87]
	v_pk_add_f32 v[98:99], v[84:85], v[86:87] neg_lo:[0,1] neg_hi:[0,1]
	v_pk_add_f32 v[84:85], v[102:103], v[72:73] op_sel:[1,0] op_sel_hi:[0,1] neg_lo:[0,1] neg_hi:[0,1]
	v_pk_add_f32 v[86:87], v[90:91], v[84:85] op_sel_hi:[1,0] neg_lo:[0,1] neg_hi:[0,1]
	v_pk_mov_b32 v[84:85], v[72:73], v[84:85] op_sel:[1,0]
	v_mov_b32_e32 v88, v89
	v_mov_b32_e32 v89, v72
	v_mul_f32_e32 v72, 0xbfb8aa3b, v74
	v_fma_f32 v73, v74, s24, -v72
	v_rndne_f32_e32 v78, v72
	v_fmac_f32_e32 v73, 0xb2a5705f, v74
	v_sub_f32_e32 v72, v72, v78
	v_add_f32_e32 v72, v72, v73
	v_exp_f32_e32 v72, v72
	v_cvt_i32_f32_e32 v73, v78
	v_mov_b32_e32 v102, v91
	v_pk_add_f32 v[84:85], v[102:103], v[84:85] neg_lo:[0,1] neg_hi:[0,1]
	v_mov_b32_e32 v86, v98
	v_ldexp_f32 v72, v72, v73
	v_cndmask_b32_e32 v72, 0, v72, vcc
	v_cmp_ngt_f32_e32 vcc, s26, v74
	v_pk_add_f32 v[100:101], v[88:89], v[84:85] neg_lo:[0,1] neg_hi:[0,1]
	v_add_f32_e32 v48, 1.0, v48
	v_cndmask_b32_e32 v102, v209, v72, vcc
	v_add_f32_e32 v74, 1.0, v102
	v_add_f32_e32 v72, -1.0, v74
	v_sub_f32_e32 v73, v72, v74
	v_add_f32_e32 v73, 1.0, v73
	v_sub_f32_e32 v72, v102, v72
	v_add_f32_e32 v78, v72, v73
	v_frexp_mant_f32_e32 v72, v74
	v_cmp_gt_f32_e32 vcc, s37, v72
	v_cvt_f64_f32_e32 v[72:73], v74
	v_frexp_exp_i32_f64_e32 v72, v[72:73]
	v_subbrev_co_u32_e32 v81, vcc, 0, v72, vcc
	v_sub_u32_e32 v72, 0, v81
	v_ldexp_f32 v74, v74, v72
	v_ldexp_f32 v72, v78, v72
	v_add_f32_e32 v78, -1.0, v74
	v_add_f32_e32 v73, 1.0, v78
	v_sub_f32_e32 v73, v74, v73
	v_add_f32_e32 v84, v72, v73
	v_add_f32_e32 v73, v78, v84
	v_sub_f32_e32 v78, v78, v73
	v_add_f32_e32 v78, v84, v78
	v_add_f32_e32 v84, 1.0, v74
	v_add_f32_e32 v85, -1.0, v84
	v_sub_f32_e32 v74, v74, v85
	v_add_f32_e32 v72, v72, v74
	v_add_f32_e32 v74, v84, v72
	v_rcp_f32_e32 v91, v74
	v_sub_f32_e32 v84, v84, v74
	v_add_f32_e32 v90, v72, v84
	v_pk_add_f32 v[104:105], v[86:87], v[100:101]
	v_mul_f32_e32 v92, v73, v91
	v_mul_f32_e32 v84, v74, v92
	v_fma_f32 v86, v92, v74, -v84
	v_fmac_f32_e32 v86, v92, v90
	v_add_f32_e32 v72, v84, v86
	v_sub_f32_e32 v85, v73, v72
	v_pk_add_f32 v[88:89], v[72:73], v[84:85] neg_lo:[0,1] neg_hi:[0,1]
	v_mov_b32_e32 v87, v72
	v_pk_add_f32 v[72:73], v[88:89], v[86:87] neg_lo:[0,1] neg_hi:[0,1]
	v_cmp_nlt_f32_e32 vcc, s25, v75
	v_add_f32_e32 v73, v78, v73
	v_add_f32_e32 v72, v72, v73
	v_add_f32_e32 v73, v85, v72
	v_mul_f32_e32 v78, v91, v73
	v_mul_f32_e32 v84, v74, v78
	v_fma_f32 v86, v78, v74, -v84
	v_fmac_f32_e32 v86, v78, v90
	v_sub_f32_e32 v74, v85, v73
	v_add_f32_e32 v74, v72, v74
	v_add_f32_e32 v72, v84, v86
	v_sub_f32_e32 v85, v73, v72
	v_pk_add_f32 v[88:89], v[72:73], v[84:85] neg_lo:[0,1] neg_hi:[0,1]
	v_mov_b32_e32 v87, v72
	v_pk_add_f32 v[72:73], v[88:89], v[86:87] neg_lo:[0,1] neg_hi:[0,1]
	v_add_f32_e32 v24, v24, v68
	v_add_f32_e32 v73, v74, v73
	v_add_f32_e32 v72, v72, v73
	v_add_f32_e32 v73, v92, v78
	v_add_f32_e32 v72, v85, v72
	v_sub_f32_e32 v74, v73, v92
	v_mul_f32_e32 v72, v91, v72
	v_sub_f32_e32 v74, v78, v74
	v_add_f32_e32 v74, v74, v72
	v_add_f32_e32 v78, v73, v74
	v_mul_f32_e32 v84, v78, v78
	v_fmamk_f32 v72, v84, 0x3e9b6dac, v195
	v_fmaak_f32 v149, v84, v72, 0x3f2aaada
	v_cvt_f32_i32_e32 v72, v81
	v_sub_f32_e32 v73, v78, v73
	v_sub_f32_e32 v73, v74, v73
	v_ldexp_f32 v74, v73, 1
	v_mul_f32_e32 v73, v78, v84
	v_pk_mul_f32 v[84:85], v[72:73], v[148:149]
	v_ldexp_f32 v87, v78, 1
	v_fma_f32 v86, v72, s38, -v84
	v_fmac_f32_e32 v86, 0xb102e308, v72
	v_pk_add_f32 v[72:73], v[84:85], v[86:87]
	v_mov_b32_e32 v88, v84
	v_sub_f32_e32 v78, v73, v87
	v_sub_f32_e32 v78, v85, v78
	v_add_f32_e32 v89, v74, v78
	v_pk_add_f32 v[90:91], v[72:73], v[84:85] neg_lo:[0,1] neg_hi:[0,1]
	v_pk_add_f32 v[92:93], v[72:73], v[88:89]
	v_mov_b32_e32 v87, v72
	v_mov_b32_e32 v91, v93
	v_pk_add_f32 v[84:85], v[86:87], v[90:91] neg_lo:[0,1] neg_hi:[0,1]
	v_pk_add_f32 v[86:87], v[86:87], v[90:91]
	v_mov_b32_e32 v88, v89
	v_pk_add_f32 v[90:91], v[86:87], v[72:73] op_sel:[1,0] op_sel_hi:[0,1] neg_lo:[0,1] neg_hi:[0,1]
	v_pk_add_f32 v[94:95], v[92:93], v[90:91] op_sel_hi:[1,0] neg_lo:[0,1] neg_hi:[0,1]
	v_pk_mov_b32 v[90:91], v[72:73], v[90:91] op_sel:[1,0]
	v_mov_b32_e32 v89, v72
	v_mul_f32_e32 v72, 0xbfb8aa3b, v75
	v_fma_f32 v73, v75, s24, -v72
	v_rndne_f32_e32 v74, v72
	v_fmac_f32_e32 v73, 0xb2a5705f, v75
	v_sub_f32_e32 v72, v72, v74
	v_add_f32_e32 v72, v72, v73
	v_exp_f32_e32 v72, v72
	v_cvt_i32_f32_e32 v73, v74
	v_mov_b32_e32 v86, v93
	v_pk_add_f32 v[90:91], v[86:87], v[90:91] neg_lo:[0,1] neg_hi:[0,1]
	v_mov_b32_e32 v94, v84
	v_ldexp_f32 v72, v72, v73
	v_cndmask_b32_e32 v72, 0, v72, vcc
	v_cmp_ngt_f32_e32 vcc, s26, v75
	v_pk_add_f32 v[88:89], v[88:89], v[90:91] neg_lo:[0,1] neg_hi:[0,1]
	v_rcp_f32_e32 v151, v48
	v_cndmask_b32_e32 v128, v209, v72, vcc
	v_add_f32_e32 v74, 1.0, v128
	v_add_f32_e32 v72, -1.0, v74
	v_sub_f32_e32 v73, v72, v74
	v_add_f32_e32 v73, 1.0, v73
	v_sub_f32_e32 v72, v128, v72
	v_add_f32_e32 v75, v72, v73
	v_frexp_mant_f32_e32 v72, v74
	v_cmp_gt_f32_e32 vcc, s37, v72
	v_cvt_f64_f32_e32 v[72:73], v74
	v_frexp_exp_i32_f64_e32 v72, v[72:73]
	v_subbrev_co_u32_e32 v78, vcc, 0, v72, vcc
	v_sub_u32_e32 v72, 0, v78
	v_ldexp_f32 v74, v74, v72
	v_ldexp_f32 v72, v75, v72
	v_add_f32_e32 v75, -1.0, v74
	v_add_f32_e32 v73, 1.0, v75
	v_sub_f32_e32 v73, v74, v73
	v_add_f32_e32 v81, v72, v73
	v_add_f32_e32 v73, v75, v81
	v_sub_f32_e32 v75, v75, v73
	v_add_f32_e32 v81, v81, v75
	v_add_f32_e32 v75, 1.0, v74
	v_add_f32_e32 v86, -1.0, v75
	v_sub_f32_e32 v74, v74, v86
	v_add_f32_e32 v72, v72, v74
	v_add_f32_e32 v86, v75, v72
	v_rcp_f32_e32 v96, v86
	v_sub_f32_e32 v74, v75, v86
	v_pk_add_f32 v[90:91], v[94:95], v[88:89]
	v_add_f32_e32 v89, v72, v74
	v_mul_f32_e32 v97, v73, v96
	v_mul_f32_e32 v74, v86, v97
	v_fma_f32 v92, v97, v86, -v74
	v_fmac_f32_e32 v92, v97, v89
	v_add_f32_e32 v72, v74, v92
	v_sub_f32_e32 v75, v73, v72
	v_pk_add_f32 v[94:95], v[72:73], v[74:75] neg_lo:[0,1] neg_hi:[0,1]
	v_mov_b32_e32 v93, v72
	v_pk_add_f32 v[72:73], v[94:95], v[92:93] neg_lo:[0,1] neg_hi:[0,1]
	v_add_f32_e32 v48, v53, v65
	v_add_f32_e32 v73, v81, v73
	v_add_f32_e32 v72, v72, v73
	v_add_f32_e32 v73, v75, v72
	v_mul_f32_e32 v81, v96, v73
	v_mul_f32_e32 v74, v86, v81
	v_fma_f32 v92, v81, v86, -v74
	v_fmac_f32_e32 v92, v81, v89
	v_sub_f32_e32 v75, v75, v73
	v_add_f32_e32 v86, v72, v75
	v_add_f32_e32 v72, v74, v92
	v_sub_f32_e32 v75, v73, v72
	v_pk_add_f32 v[94:95], v[72:73], v[74:75] neg_lo:[0,1] neg_hi:[0,1]
	v_mov_b32_e32 v93, v72
	v_pk_add_f32 v[72:73], v[94:95], v[92:93] neg_lo:[0,1] neg_hi:[0,1]
	v_mul_f32_e32 v24, 0xbfb8aa3b, v24
	v_add_f32_e32 v73, v86, v73
	v_add_f32_e32 v72, v72, v73
	v_add_f32_e32 v73, v97, v81
	v_add_f32_e32 v72, v75, v72
	v_sub_f32_e32 v74, v73, v97
	v_mul_f32_e32 v72, v96, v72
	v_sub_f32_e32 v74, v81, v74
	v_add_f32_e32 v74, v74, v72
	v_add_f32_e32 v75, v73, v74
	v_mul_f32_e32 v81, v75, v75
	v_fmamk_f32 v72, v81, 0x3e9b6dac, v195
	v_fmaak_f32 v149, v81, v72, 0x3f2aaada
	v_cvt_f32_i32_e32 v72, v78
	v_sub_f32_e32 v73, v75, v73
	v_sub_f32_e32 v73, v74, v73
	v_ldexp_f32 v78, v73, 1
	v_mul_f32_e32 v73, v75, v81
	v_ldexp_f32 v93, v75, 1
	v_pk_mul_f32 v[74:75], v[72:73], v[148:149]
	v_mul_f32_e32 v48, 0xbfb8aa3b, v48
	v_fma_f32 v92, v72, s38, -v74
	v_fmac_f32_e32 v92, 0xb102e308, v72
	v_pk_add_f32 v[72:73], v[74:75], v[92:93]
	v_mov_b32_e32 v94, v74
	v_sub_f32_e32 v81, v73, v93
	v_sub_f32_e32 v81, v75, v81
	v_add_f32_e32 v95, v78, v81
	v_pk_add_f32 v[96:97], v[72:73], v[74:75] neg_lo:[0,1] neg_hi:[0,1]
	v_pk_add_f32 v[110:111], v[72:73], v[94:95]
	v_mov_b32_e32 v93, v72
	v_mov_b32_e32 v97, v111
	v_pk_add_f32 v[74:75], v[92:93], v[96:97] neg_lo:[0,1] neg_hi:[0,1]
	v_pk_add_f32 v[96:97], v[92:93], v[96:97]
	v_mov_b32_e32 v94, v95
	v_pk_add_f32 v[92:93], v[96:97], v[72:73] op_sel:[1,0] op_sel_hi:[0,1] neg_lo:[0,1] neg_hi:[0,1]
	v_pk_add_f32 v[112:113], v[110:111], v[92:93] op_sel_hi:[1,0] neg_lo:[0,1] neg_hi:[0,1]
	v_pk_mov_b32 v[92:93], v[72:73], v[92:93] op_sel:[1,0]
	v_mov_b32_e32 v95, v72
	v_lshl_add_u64 v[72:73], v[106:107], 1, v[140:141]
	v_ashrrev_i32_e32 v78, 4, v108
	v_add_co_u32_e32 v108, vcc, s33, v72
	v_mov_b32_e32 v96, v111
	s_nop 0
	v_addc_co_u32_e32 v109, vcc, 0, v73, vcc
	global_load_dwordx2 v[110:111], v[108:109], off offset:32
	global_load_dwordx2 v[106:107], v[72:73], off offset:32
	v_rcp_f32_e32 v108, v56
	v_mul_f32_e32 v56, 0xbfb8aa3b, v57
	v_exp_f32_e32 v56, v56
	v_exp_f32_e32 v24, v24
	v_exp_f32_e32 v48, v48
	v_add_f32_e32 v57, v58, v70
	v_add_f32_e32 v56, 1.0, v56
	v_rcp_f32_e32 v143, v56
	v_add_f32_e32 v56, v62, v66
	v_mul_f32_e32 v56, 0xbfb8aa3b, v56
	v_exp_f32_e32 v56, v56
	v_pk_add_f32 v[92:93], v[96:97], v[92:93] neg_lo:[0,1] neg_hi:[0,1]
	v_add_f32_e32 v24, 1.0, v24
	v_pk_add_f32 v[92:93], v[94:95], v[92:93] neg_lo:[0,1] neg_hi:[0,1]
	v_add_f32_e32 v56, 1.0, v56
	v_rcp_f32_e32 v61, v56
	v_mul_f32_e32 v56, 0xbfb8aa3b, v57
	v_exp_f32_e32 v56, v56
	v_mov_b32_e32 v112, v74
	v_add_f32_e32 v49, v49, v69
	v_add_f32_e32 v48, 1.0, v48
	v_rcp_f32_e32 v156, v24
	v_add_f32_e32 v24, v29, v65
	v_pk_add_f32 v[94:95], v[112:113], v[92:93]
	v_mul_f32_e32 v24, 0xbfb8aa3b, v24
	v_exp_f32_e32 v24, v24
	v_add_f32_e32 v56, 1.0, v56
	v_add_f32_e32 v60, v60, v64
	v_rcp_f32_e32 v137, v56
	v_add_f32_e32 v56, v63, v67
	v_mul_f32_e32 v60, 0xbfb8aa3b, v60
	v_mul_f32_e32 v56, 0xbfb8aa3b, v56
	v_exp_f32_e32 v60, v60
	v_exp_f32_e32 v56, v56
	v_add_f32_e32 v25, v25, v69
	v_add_f32_e32 v24, 1.0, v24
	v_add_f32_e32 v40, v40, v68
	v_rcp_f32_e32 v116, v24
	v_mul_f32_e32 v24, 0xbfb8aa3b, v25
	v_mul_f32_e32 v40, 0xbfb8aa3b, v40
	v_exp_f32_e32 v24, v24
	v_exp_f32_e32 v40, v40
	v_add_f32_e32 v60, 1.0, v60
	v_add_f32_e32 v57, v59, v71
	v_add_f32_e32 v56, 1.0, v56
	v_rcp_f32_e32 v109, v60
	v_rcp_f32_e32 v60, v56
	v_mul_f32_e32 v56, 0xbfb8aa3b, v57
	v_exp_f32_e32 v56, v56
	v_add_f32_e32 v24, 1.0, v24
	v_add_f32_e32 v50, v50, v70
	v_add_f32_e32 v40, 1.0, v40
	v_rcp_f32_e32 v25, v24
	v_add_f32_e32 v24, v30, v66
	v_rcp_f32_e32 v153, v40
	v_add_f32_e32 v40, v45, v65
	v_mul_f32_e32 v24, 0xbfb8aa3b, v24
	v_add_f32_e32 v16, v16, v68
	v_mul_f32_e32 v40, 0xbfb8aa3b, v40
	v_exp_f32_e32 v24, v24
	v_mul_f32_e32 v16, 0xbfb8aa3b, v16
	v_add_f32_e32 v56, 1.0, v56
	v_exp_f32_e32 v40, v40
	v_exp_f32_e32 v16, v16
	v_rcp_f32_e32 v136, v56
	v_add_u32_e32 v56, v78, v132
	v_ashrrev_i32_e32 v57, 31, v56
	v_lshlrev_b64 v[56:57], 16, v[56:57]
	v_add_f32_e32 v26, v26, v70
	v_add_f32_e32 v24, 1.0, v24
	v_or3_b32 v58, v56, v133, v146
	v_add_f32_e32 v41, v41, v69
	v_add_f32_e32 v40, 1.0, v40
	v_add_f32_e32 v16, 1.0, v16
	v_rcp_f32_e32 v112, v40
	v_mul_f32_e32 v40, 0xbfb8aa3b, v41
	v_rcp_f32_e32 v29, v16
	v_add_f32_e32 v16, v21, v65
	s_waitcnt vmcnt(1)
	v_lshlrev_b32_e32 v149, 16, v110
	v_and_b32_e32 v93, 0xffff0000, v110
	v_rcp_f32_e32 v110, v48
	v_mul_f32_e32 v48, 0xbfb8aa3b, v49
	v_exp_f32_e32 v48, v48
	v_exp_f32_e32 v40, v40
	v_mul_f32_e32 v16, 0xbfb8aa3b, v16
	v_exp_f32_e32 v16, v16
	v_add_f32_e32 v48, 1.0, v48
	v_rcp_f32_e32 v150, v48
	v_add_f32_e32 v48, v54, v66
	v_mul_f32_e32 v48, 0xbfb8aa3b, v48
	v_exp_f32_e32 v48, v48
	v_add_f32_e32 v40, 1.0, v40
	v_rcp_f32_e32 v152, v40
	v_add_f32_e32 v40, v46, v66
	v_add_f32_e32 v48, 1.0, v48
	v_rcp_f32_e32 v49, v48
	v_mul_f32_e32 v48, 0xbfb8aa3b, v50
	v_exp_f32_e32 v48, v48
	v_add_f32_e32 v17, v17, v69
	v_add_f32_e32 v16, 1.0, v16
	v_add_f32_e32 v8, v8, v68
	v_add_f32_e32 v48, 1.0, v48
	v_rcp_f32_e32 v133, v48
	v_add_f32_e32 v48, v55, v67
	v_rcp_f32_e32 v55, v24
	v_mul_f32_e32 v24, 0xbfb8aa3b, v26
	v_exp_f32_e32 v24, v24
	v_mul_f32_e32 v40, 0xbfb8aa3b, v40
	v_rcp_f32_e32 v118, v16
	v_mul_f32_e32 v16, 0xbfb8aa3b, v17
	v_add_f32_e32 v24, 1.0, v24
	v_rcp_f32_e32 v141, v24
	v_add_f32_e32 v24, v31, v67
	v_mul_f32_e32 v24, 0xbfb8aa3b, v24
	v_exp_f32_e32 v24, v24
	v_mul_f32_e32 v8, 0xbfb8aa3b, v8
	v_exp_f32_e32 v40, v40
	v_exp_f32_e32 v16, v16
	v_exp_f32_e32 v8, v8
	v_add_f32_e32 v26, v27, v71
	v_add_f32_e32 v24, 1.0, v24
	v_add_f32_e32 v41, v42, v70
	v_add_f32_e32 v40, 1.0, v40
	v_rcp_f32_e32 v54, v24
	v_mul_f32_e32 v24, 0xbfb8aa3b, v26
	v_or3_b32 v26, v56, v127, v146
	v_mov_b32_e32 v27, v57
	v_add_f32_e32 v16, 1.0, v16
	v_add_f32_e32 v8, 1.0, v8
	s_waitcnt vmcnt(0)
	v_lshlrev_b32_e32 v130, 16, v107
	v_and_b32_e32 v96, 0xffff0000, v107
	v_rcp_f32_e32 v107, v40
	v_mul_f32_e32 v40, 0xbfb8aa3b, v41
	v_add_f32_e32 v41, v43, v71
	v_lshl_add_u64 v[42:43], v[26:27], 3, s[14:15]
	v_rcp_f32_e32 v27, v16
	v_add_f32_e32 v16, v22, v66
	v_rcp_f32_e32 v157, v8
	v_add_f32_e32 v8, v13, v65
	v_mul_f32_e32 v16, 0xbfb8aa3b, v16
	v_mul_f32_e32 v8, 0xbfb8aa3b, v8
	v_exp_f32_e32 v16, v16
	v_exp_f32_e32 v8, v8
	v_add_f32_e32 v17, v18, v70
	v_add_f32_e32 v9, v9, v69
	v_add_f32_e32 v16, 1.0, v16
	v_add_f32_e32 v8, 1.0, v8
	v_rcp_f32_e32 v53, v16
	v_mul_f32_e32 v16, 0xbfb8aa3b, v17
	v_rcp_f32_e32 v120, v8
	v_mul_f32_e32 v8, 0xbfb8aa3b, v9
	v_exp_f32_e32 v16, v16
	v_exp_f32_e32 v8, v8
	v_add_f32_e32 v52, v52, v64
	v_mul_f32_e32 v52, 0xbfb8aa3b, v52
	v_add_f32_e32 v16, 1.0, v16
	v_add_f32_e32 v8, 1.0, v8
	v_rcp_f32_e32 v142, v16
	v_add_f32_e32 v16, v23, v67
	v_rcp_f32_e32 v31, v8
	v_add_f32_e32 v8, v14, v66
	v_mul_f32_e32 v16, 0xbfb8aa3b, v16
	v_mul_f32_e32 v8, 0xbfb8aa3b, v8
	v_add_f32_e32 v0, v0, v64
	v_exp_f32_e32 v52, v52
	v_exp_f32_e32 v40, v40
	v_exp_f32_e32 v16, v16
	v_exp_f32_e32 v8, v8
	v_mul_f32_e32 v0, 0xbfb8aa3b, v0
	v_exp_f32_e32 v0, v0
	v_add_f32_e32 v52, 1.0, v52
	v_add_f32_e32 v40, 1.0, v40
	v_add_f32_e32 v17, v19, v71
	v_add_f32_e32 v16, 1.0, v16
	v_add_f32_e32 v9, v10, v70
	v_add_f32_e32 v8, 1.0, v8
	v_lshlrev_b32_e32 v132, 16, v111
	v_and_b32_e32 v131, 0xffff0000, v111
	v_rcp_f32_e32 v111, v52
	v_rcp_f32_e32 v139, v40
	v_add_f32_e32 v40, v47, v67
	v_rcp_f32_e32 v52, v16
	v_mul_f32_e32 v16, 0xbfb8aa3b, v17
	v_rcp_f32_e32 v47, v8
	v_mul_f32_e32 v8, 0xbfb8aa3b, v9
	v_add_f32_e32 v4, v4, v68
	v_add_f32_e32 v0, 1.0, v0
	v_exp_f32_e32 v16, v16
	v_exp_f32_e32 v8, v8
	v_rcp_f32_e32 v13, v0
	v_mul_f32_e32 v0, 0xbfb8aa3b, v4
	v_exp_f32_e32 v0, v0
	v_add_f32_e32 v16, 1.0, v16
	v_add_f32_e32 v8, 1.0, v8
	v_rcp_f32_e32 v127, v16
	v_or3_b32 v16, v56, v134, v146
	v_rcp_f32_e32 v134, v8
	v_add_f32_e32 v8, v15, v67
	v_add_f32_e32 v0, 1.0, v0
	v_add_f32_e32 v12, v12, v64
	v_mul_f32_e32 v8, 0xbfb8aa3b, v8
	v_rcp_f32_e32 v14, v0
	v_add_f32_e32 v0, v1, v65
	v_mul_f32_e32 v12, 0xbfb8aa3b, v12
	v_exp_f32_e32 v8, v8
	v_mul_f32_e32 v0, 0xbfb8aa3b, v0
	v_exp_f32_e32 v12, v12
	v_exp_f32_e32 v0, v0
	v_add_f32_e32 v9, v11, v71
	v_add_f32_e32 v8, 1.0, v8
	v_add_f32_e32 v36, v36, v64
	v_add_f32_e32 v32, v32, v68
	v_add_f32_e32 v12, 1.0, v12
	v_rcp_f32_e32 v46, v8
	v_mul_f32_e32 v8, 0xbfb8aa3b, v9
	v_add_f32_e32 v1, v5, v69
	v_add_f32_e32 v0, 1.0, v0
	v_mul_f32_e32 v36, 0xbfb8aa3b, v36
	v_mul_f32_e32 v32, 0xbfb8aa3b, v32
	v_rcp_f32_e32 v121, v12
	v_exp_f32_e32 v8, v8
	v_rcp_f32_e32 v12, v0
	v_mul_f32_e32 v0, 0xbfb8aa3b, v1
	v_exp_f32_e32 v36, v36
	v_exp_f32_e32 v32, v32
	v_exp_f32_e32 v0, v0
	v_add_f32_e32 v44, v44, v64
	v_add_f32_e32 v20, v20, v64
	v_mul_f32_e32 v44, 0xbfb8aa3b, v44
	v_mul_f32_e32 v20, 0xbfb8aa3b, v20
	v_add_f32_e32 v8, 1.0, v8
	v_exp_f32_e32 v44, v44
	v_add_f32_e32 v36, 1.0, v36
	v_add_f32_e32 v32, 1.0, v32
	v_exp_f32_e32 v20, v20
	v_rcp_f32_e32 v15, v8
	v_or3_b32 v8, v56, v135, v146
	v_mov_b32_e32 v9, v57
	v_add_f32_e32 v0, 1.0, v0
	v_rcp_f32_e32 v115, v36
	v_rcp_f32_e32 v155, v32
	v_add_f32_e32 v32, v37, v65
	v_lshl_add_u64 v[36:37], v[8:9], 3, s[14:15]
	v_rcp_f32_e32 v4, v0
	v_mov_b32_e32 v0, v104
	v_mov_b32_e32 v1, v82
	v_mov_b32_e32 v8, v105
	v_mov_b32_e32 v9, v83
	v_pk_add_f32 v[8:9], v[0:1], v[8:9]
	v_mov_b32_e32 v78, v103
	v_pk_add_f32 v[10:11], v[78:79], v[8:9]
	v_mov_b32_e32 v77, v79
	v_mov_b32_e32 v99, v103
	v_add_f32_e32 v44, 1.0, v44
	v_add_f32_e32 v20, 1.0, v20
	v_mov_b32_e32 v17, v57
	v_mov_b32_e32 v83, v11
	v_mov_b32_e32 v105, v10
	v_rcp_f32_e32 v113, v44
	v_rcp_f32_e32 v119, v20
	v_lshl_add_u64 v[44:45], v[16:17], 3, s[14:15]
	v_pk_add_f32 v[16:17], v[82:83], v[76:77] neg_lo:[0,1] neg_hi:[0,1]
	v_pk_add_f32 v[20:21], v[104:105], v[98:99] neg_lo:[0,1] neg_hi:[0,1]
	v_mov_b32_e32 v81, v9
	v_mov_b32_e32 v22, v20
	v_mov_b32_e32 v23, v16
	v_mov_b32_e32 v101, v8
	v_mul_f32_e32 v32, 0xbfb8aa3b, v32
	v_pk_add_f32 v[18:19], v[80:81], v[16:17] neg_lo:[0,1] neg_hi:[0,1]
	v_pk_add_f32 v[0:1], v[0:1], v[22:23] neg_lo:[0,1] neg_hi:[0,1]
	v_mov_b32_e32 v99, v76
	v_pk_add_f32 v[8:9], v[100:101], v[20:21] neg_lo:[0,1] neg_hi:[0,1]
	v_exp_f32_e32 v32, v32
	v_pk_add_f32 v[0:1], v[98:99], v[0:1] neg_lo:[0,1] neg_hi:[0,1]
	v_mov_b32_e32 v16, v8
	v_mov_b32_e32 v17, v18
	v_pk_add_f32 v[0:1], v[16:17], v[0:1]
	v_mov_b32_e32 v18, v9
	v_pk_add_f32 v[0:1], v[0:1], v[18:19]
	v_cmp_neq_f32_e32 vcc, s27, v129
	v_pk_add_f32 v[0:1], v[10:11], v[0:1]
	v_add_f32_e32 v33, v33, v69
	v_add_f32_e32 v32, 1.0, v32
	v_cndmask_b32_e32 v0, v209, v0, vcc
	v_cmp_neq_f32_e32 vcc, s27, v123
	v_rcp_f32_e32 v114, v32
	v_mul_f32_e32 v32, 0xbfb8aa3b, v33
	v_cndmask_b32_e32 v1, v209, v1, vcc
	v_cmp_lt_f32_e64 vcc, |v129|, s39
	v_cmp_lt_f32_e64 s[0:1], |v123|, s39
	v_exp_f32_e32 v32, v32
	v_cndmask_b32_e32 v0, v0, v129, vcc
	v_cndmask_b32_e64 v1, v1, v123, s[0:1]
	v_pk_mul_f32 v[8:9], v[108:109], s[44:45] op_sel_hi:[1,0]
	v_add_f32_e32 v32, 1.0, v32
	v_pk_mul_f32 v[10:11], v[8:9], v[0:1]
	v_rcp_f32_e32 v154, v32
	v_mul_f32_e32 v5, 0x3fb8aa3b, v11
	v_exp_f32_e32 v8, v5
	v_pk_add_f32 v[16:17], v[10:11], v[10:11]
	v_add_f32_e32 v32, v38, v66
	v_fmamk_f32 v9, v17, 0x3d2aaaab, v196
	v_fma_f32 v9, v17, v9, 0.5
	v_mul_f32_e32 v32, 0xbfb8aa3b, v32
	v_fma_f32 v9, v17, v9, 1.0
	v_exp_f32_e32 v32, v32
	v_fma_f32 v5, -v8, v8, 1.0
	v_mul_f32_e64 v9, v9, -v17
	v_cmp_lt_f32_e64 s[0:1], s40, v17
	v_add_f32_e32 v33, v34, v70
	v_add_f32_e32 v32, 1.0, v32
	v_cndmask_b32_e64 v5, v5, v9, s[0:1]
	v_max_f32_e32 v5, 0, v5
	v_sqrt_f32_e32 v5, v5
	v_rcp_f32_e32 v63, v32
	v_mul_f32_e32 v32, 0xbfb8aa3b, v33
	v_exp_f32_e32 v32, v32
	v_lshlrev_b32_e32 v89, 16, v106
	v_mul_f32_e32 v5, v145, v5
	v_mul_f32_e32 v9, v5, v89
	v_mul_f32_e32 v5, 0x3fb8aa3b, v10
	v_exp_f32_e32 v10, v5
	v_add_f32_e32 v32, 1.0, v32
	v_fmamk_f32 v11, v16, 0x3d2aaaab, v196
	v_rcp_f32_e32 v140, v32
	v_add_f32_e32 v32, v39, v67
	v_fma_f32 v11, v16, v11, 0.5
	v_mul_f32_e32 v40, 0xbfb8aa3b, v40
	v_mul_f32_e32 v32, 0xbfb8aa3b, v32
	v_fma_f32 v11, v16, v11, 1.0
	v_exp_f32_e32 v40, v40
	v_exp_f32_e32 v32, v32
	v_cmp_lt_f32_e32 vcc, s40, v16
	v_fma_f32 v5, -v10, v10, 1.0
	v_mul_f32_e64 v11, v11, -v16
	v_cndmask_b32_e32 v5, v5, v11, vcc
	v_max_f32_e32 v5, 0, v5
	v_sqrt_f32_e32 v5, v5
	v_add_f32_e32 v50, v51, v71
	v_add_f32_e32 v40, 1.0, v40
	v_add_f32_e32 v33, v35, v71
	v_add_f32_e32 v32, 1.0, v32
	v_and_b32_e32 v86, 0xffff0000, v106
	v_mul_f32_e32 v50, 0xbfb8aa3b, v50
	v_rcp_f32_e32 v106, v40
	v_mul_f32_e32 v40, 0xbfb8aa3b, v41
	v_rcp_f32_e32 v62, v32
	v_mul_f32_e32 v32, 0xbfb8aa3b, v33
	v_exp_f32_e32 v50, v50
	v_exp_f32_e32 v40, v40
	v_exp_f32_e32 v32, v32
	v_mov_b32_e32 v59, v57
	v_mul_f32_e32 v5, v143, v5
	v_lshl_add_u64 v[58:59], v[58:59], 3, s[14:15]
	v_mul_f32_e32 v11, v5, v86
	global_store_dwordx4 v[58:59], v[8:11], off
	v_add_f32_e32 v50, 1.0, v50
	v_add_f32_e32 v40, 1.0, v40
	v_pk_mul_f32 v[8:9], v[110:111], s[44:45] op_sel_hi:[1,0]
	v_add_f32_e32 v32, 1.0, v32
	v_pk_mul_f32 v[8:9], v[8:9], v[0:1]
	v_rcp_f32_e32 v138, v50
	v_or3_b32 v50, v56, v124, v146
	v_rcp_f32_e32 v124, v40
	v_or3_b32 v40, v56, v125, v146
	v_rcp_f32_e32 v125, v32
	v_or3_b32 v32, v56, v126, v146
	v_mov_b32_e32 v33, v57
	v_mul_f32_e32 v5, 0x3fb8aa3b, v9
	v_lshl_add_u64 v[38:39], v[32:33], 3, s[14:15]
	v_exp_f32_e32 v32, v5
	v_pk_add_f32 v[10:11], v[8:9], v[8:9]
	v_add_f32_e32 v28, v28, v64
	v_fmamk_f32 v9, v11, 0x3d2aaaab, v196
	v_fma_f32 v9, v11, v9, 0.5
	v_fma_f32 v9, v11, v9, 1.0
	v_fma_f32 v5, -v32, v32, 1.0
	v_mul_f32_e64 v9, v9, -v11
	v_cmp_lt_f32_e64 s[0:1], s40, v11
	v_cmp_lt_f32_e32 vcc, s40, v10
	v_mul_f32_e32 v28, 0xbfb8aa3b, v28
	v_cndmask_b32_e64 v5, v5, v9, s[0:1]
	v_max_f32_e32 v5, 0, v5
	v_sqrt_f32_e32 v5, v5
	v_exp_f32_e32 v28, v28
	v_exp_f32_e32 v24, v24
	v_pk_mul_f32 v[12:13], v[12:13], s[44:45] op_sel_hi:[1,0]
	v_mul_f32_e32 v5, v151, v5
	v_mul_f32_e32 v33, v5, v149
	v_mul_f32_e32 v5, 0x3fb8aa3b, v8
	v_exp_f32_e32 v34, v5
	v_fmamk_f32 v8, v10, 0x3d2aaaab, v196
	v_fma_f32 v8, v10, v8, 0.5
	v_fma_f32 v8, v10, v8, 1.0
	v_fma_f32 v5, -v34, v34, 1.0
	v_mul_f32_e64 v8, v8, -v10
	v_cndmask_b32_e32 v5, v5, v8, vcc
	v_max_f32_e32 v5, 0, v5
	v_sqrt_f32_e32 v5, v5
	v_pk_mul_f32 v[8:9], v[112:113], s[44:45] op_sel_hi:[1,0]
	v_add_f32_e32 v28, 1.0, v28
	v_pk_mul_f32 v[8:9], v[8:9], v[0:1]
	v_mul_f32_e32 v5, v150, v5
	v_mul_f32_e32 v35, v5, v93
	v_mul_f32_e32 v5, 0x3fb8aa3b, v9
	v_rcp_f32_e32 v117, v28
	v_exp_f32_e32 v28, v5
	v_pk_add_f32 v[10:11], v[8:9], v[8:9]
	v_add_f32_e32 v24, 1.0, v24
	v_fmamk_f32 v9, v11, 0x3d2aaaab, v196
	v_fma_f32 v9, v11, v9, 0.5
	v_fma_f32 v9, v11, v9, 1.0
	v_fma_f32 v5, -v28, v28, 1.0
	v_mul_f32_e64 v9, v9, -v11
	v_cmp_lt_f32_e64 s[0:1], s40, v11
	v_cmp_lt_f32_e32 vcc, s40, v10
	v_rcp_f32_e32 v126, v24
	v_cndmask_b32_e64 v5, v5, v9, s[0:1]
	v_max_f32_e32 v5, 0, v5
	v_sqrt_f32_e32 v5, v5
	v_mov_b32_e32 v86, v97
	v_mov_b32_e32 v85, v87
	v_mov_b32_e32 v75, v97
	v_mul_f32_e32 v68, v153, v5
	v_mul_f32_e32 v5, 0x3fb8aa3b, v8
	v_exp_f32_e32 v30, v5
	v_fmamk_f32 v8, v10, 0x3d2aaaab, v196
	v_fma_f32 v8, v10, v8, 0.5
	v_fma_f32 v8, v10, v8, 1.0
	v_fma_f32 v5, -v30, v30, 1.0
	v_mul_f32_e64 v8, v8, -v10
	v_cndmask_b32_e32 v5, v5, v8, vcc
	v_max_f32_e32 v5, 0, v5
	v_sqrt_f32_e32 v5, v5
	v_pk_mul_f32 v[8:9], v[114:115], s[44:45] op_sel_hi:[1,0]
	v_pk_mul_f32 v[60:61], v[60:61], s[44:45] op_sel_hi:[1,0]
	v_pk_mul_f32 v[8:9], v[8:9], v[0:1]
	v_mul_f32_e32 v69, v152, v5
	v_mul_f32_e32 v5, 0x3fb8aa3b, v9
	v_exp_f32_e32 v24, v5
	v_pk_add_f32 v[10:11], v[8:9], v[8:9]
	v_mul_f32_e32 v48, 0xbfb8aa3b, v48
	v_fmamk_f32 v9, v11, 0x3d2aaaab, v196
	v_fma_f32 v9, v11, v9, 0.5
	v_fma_f32 v9, v11, v9, 1.0
	v_fma_f32 v5, -v24, v24, 1.0
	v_mul_f32_e64 v9, v9, -v11
	v_cmp_lt_f32_e64 s[0:1], s40, v11
	v_cmp_lt_f32_e32 vcc, s40, v10
	v_exp_f32_e32 v48, v48
	v_cndmask_b32_e64 v5, v5, v9, s[0:1]
	v_max_f32_e32 v5, 0, v5
	v_sqrt_f32_e32 v5, v5
	v_add_f32_e32 v48, 1.0, v48
	v_mov_b32_e32 v51, v57
	v_mov_b32_e32 v41, v57
	v_mul_f32_e32 v64, v155, v5
	v_mul_f32_e32 v5, 0x3fb8aa3b, v8
	v_exp_f32_e32 v26, v5
	v_fmamk_f32 v8, v10, 0x3d2aaaab, v196
	v_fma_f32 v8, v10, v8, 0.5
	v_fma_f32 v8, v10, v8, 1.0
	v_fma_f32 v5, -v26, v26, 1.0
	v_mul_f32_e64 v8, v8, -v10
	v_cndmask_b32_e32 v5, v5, v8, vcc
	v_max_f32_e32 v5, 0, v5
	v_sqrt_f32_e32 v5, v5
	v_pk_mul_f32 v[8:9], v[116:117], s[44:45] op_sel_hi:[1,0]
	v_rcp_f32_e32 v48, v48
	v_pk_mul_f32 v[8:9], v[8:9], v[0:1]
	v_mul_f32_e32 v65, v154, v5
	v_mul_f32_e32 v5, 0x3fb8aa3b, v9
	v_exp_f32_e32 v20, v5
	v_pk_add_f32 v[10:11], v[8:9], v[8:9]
	v_lshl_add_u64 v[50:51], v[50:51], 3, s[14:15]
	v_fmamk_f32 v9, v11, 0x3d2aaaab, v196
	v_fma_f32 v9, v11, v9, 0.5
	v_fma_f32 v9, v11, v9, 1.0
	v_fma_f32 v5, -v20, v20, 1.0
	v_mul_f32_e64 v9, v9, -v11
	v_cmp_lt_f32_e64 s[0:1], s40, v11
	v_cmp_lt_f32_e32 vcc, s40, v10
	v_lshl_add_u64 v[40:41], v[40:41], 3, s[14:15]
	v_cndmask_b32_e64 v5, v5, v9, s[0:1]
	v_max_f32_e32 v5, 0, v5
	v_sqrt_f32_e32 v5, v5
	s_nop 0
	v_mul_f32_e32 v21, v156, v5
	v_mul_f32_e32 v5, 0x3fb8aa3b, v8
	v_exp_f32_e32 v22, v5
	v_fmamk_f32 v8, v10, 0x3d2aaaab, v196
	v_fma_f32 v8, v10, v8, 0.5
	v_fma_f32 v8, v10, v8, 1.0
	v_fma_f32 v5, -v22, v22, 1.0
	v_mul_f32_e64 v8, v8, -v10
	v_cndmask_b32_e32 v5, v5, v8, vcc
	v_max_f32_e32 v5, 0, v5
	v_sqrt_f32_e32 v5, v5
	v_pk_mul_f32 v[8:9], v[118:119], s[44:45] op_sel_hi:[1,0]
	v_mul_f32_e32 v23, v25, v5
	v_pk_mul_f32 v[8:9], v[8:9], v[0:1]
	s_nop 0
	v_mul_f32_e32 v5, 0x3fb8aa3b, v9
	v_exp_f32_e32 v16, v5
	v_pk_add_f32 v[10:11], v[8:9], v[8:9]
	v_fma_f32 v5, -v16, v16, 1.0
	v_fmamk_f32 v9, v11, 0x3d2aaaab, v196
	v_fma_f32 v9, v11, v9, 0.5
	v_fma_f32 v9, v11, v9, 1.0
	v_mul_f32_e64 v9, v9, -v11
	v_cmp_lt_f32_e64 s[0:1], s40, v11
	v_cmp_lt_f32_e32 vcc, s40, v10
	s_nop 0
	v_cndmask_b32_e64 v5, v5, v9, s[0:1]
	v_max_f32_e32 v5, 0, v5
	v_sqrt_f32_e32 v5, v5
	s_nop 0
	v_mul_f32_e32 v17, v29, v5
	v_mul_f32_e32 v5, 0x3fb8aa3b, v8
	v_exp_f32_e32 v18, v5
	v_fmamk_f32 v8, v10, 0x3d2aaaab, v196
	v_fma_f32 v8, v10, v8, 0.5
	v_fma_f32 v8, v10, v8, 1.0
	v_fma_f32 v5, -v18, v18, 1.0
	v_mul_f32_e64 v8, v8, -v10
	v_cndmask_b32_e32 v5, v5, v8, vcc
	v_max_f32_e32 v5, 0, v5
	v_sqrt_f32_e32 v5, v5
	v_pk_mul_f32 v[8:9], v[120:121], s[44:45] op_sel_hi:[1,0]
	v_mul_f32_e32 v19, v27, v5
	v_pk_mul_f32 v[10:11], v[8:9], v[0:1]
	v_pk_mul_f32 v[0:1], v[12:13], v[0:1]
	v_mul_f32_e32 v5, 0x3fb8aa3b, v11
	v_exp_f32_e32 v8, v5
	v_pk_add_f32 v[76:77], v[10:11], v[10:11]
	v_fma_f32 v5, -v8, v8, 1.0
	v_fmamk_f32 v9, v77, 0x3d2aaaab, v196
	v_fma_f32 v9, v77, v9, 0.5
	v_fma_f32 v9, v77, v9, 1.0
	v_mul_f32_e64 v9, v9, -v77
	v_cmp_lt_f32_e64 s[0:1], s40, v77
	v_fmamk_f32 v11, v76, 0x3d2aaaab, v196
	v_fma_f32 v11, v76, v11, 0.5
	v_cndmask_b32_e64 v5, v5, v9, s[0:1]
	v_max_f32_e32 v5, 0, v5
	v_sqrt_f32_e32 v5, v5
	v_fma_f32 v11, v76, v11, 1.0
	v_cmp_lt_f32_e32 vcc, s40, v76
	v_mul_f32_e64 v11, v11, -v76
	v_mul_f32_e32 v9, v157, v5
	v_mul_f32_e32 v5, 0x3fb8aa3b, v10
	v_exp_f32_e32 v10, v5
	v_pk_add_f32 v[76:77], v[0:1], v[0:1]
	v_mul_f32_e32 v0, 0x3fb8aa3b, v0
	v_cmp_lt_f32_e64 s[0:1], s40, v77
	v_fma_f32 v5, -v10, v10, 1.0
	v_cndmask_b32_e32 v5, v5, v11, vcc
	v_max_f32_e32 v5, 0, v5
	v_sqrt_f32_e32 v5, v5
	v_cmp_lt_f32_e32 vcc, s40, v76
	v_mul_f32_e32 v11, v31, v5
	v_mul_f32_e32 v5, 0x3fb8aa3b, v1
	v_exp_f32_e32 v12, v5
	v_fmamk_f32 v1, v77, 0x3d2aaaab, v196
	v_fma_f32 v1, v77, v1, 0.5
	v_fma_f32 v1, v77, v1, 1.0
	v_fma_f32 v5, -v12, v12, 1.0
	v_mul_f32_e64 v1, v1, -v77
	v_cndmask_b32_e64 v1, v5, v1, s[0:1]
	v_max_f32_e32 v1, 0, v1
	v_sqrt_f32_e32 v1, v1
	v_cmp_lt_f32_e64 s[0:1], |v102|, s39
	v_mul_f32_e32 v5, v14, v1
	v_exp_f32_e32 v14, v0
	v_fmamk_f32 v1, v76, 0x3d2aaaab, v196
	v_fma_f32 v1, v76, v1, 0.5
	v_fma_f32 v1, v76, v1, 1.0
	v_fma_f32 v0, -v14, v14, 1.0
	v_mul_f32_e64 v1, v1, -v76
	v_cndmask_b32_e32 v0, v0, v1, vcc
	v_max_f32_e32 v0, 0, v0
	v_sqrt_f32_e32 v0, v0
	v_cmp_neq_f32_e32 vcc, s27, v128
	v_mul_f32_e32 v4, v4, v0
	v_add_f32_e32 v0, v2, v66
	v_mul_f32_e32 v0, 0xbfb8aa3b, v0
	v_exp_f32_e32 v0, v0
	v_add_f32_e32 v2, v6, v70
	v_mov_b32_e32 v66, v95
	v_add_f32_e32 v0, 1.0, v0
	v_rcp_f32_e32 v1, v0
	v_mul_f32_e32 v0, 0xbfb8aa3b, v2
	v_add_f32_e32 v2, v7, v71
	v_mul_f32_e32 v2, 0xbfb8aa3b, v2
	v_exp_f32_e32 v0, v0
	v_exp_f32_e32 v2, v2
	v_add_f32_e32 v0, 1.0, v0
	v_add_f32_e32 v2, 1.0, v2
	v_rcp_f32_e32 v6, v0
	v_add_f32_e32 v0, v3, v67
	v_rcp_f32_e32 v7, v2
	v_mov_b32_e32 v2, v94
	v_mov_b32_e32 v3, v90
	v_mov_b32_e32 v67, v91
	v_pk_add_f32 v[66:67], v[2:3], v[66:67]
	v_mul_f32_e32 v0, 0xbfb8aa3b, v0
	v_pk_add_f32 v[70:71], v[86:87], v[66:67]
	v_mov_b32_e32 v89, v67
	v_mov_b32_e32 v91, v71
	v_mov_b32_e32 v95, v70
	v_pk_add_f32 v[76:77], v[90:91], v[84:85] neg_lo:[0,1] neg_hi:[0,1]
	v_pk_add_f32 v[80:81], v[94:95], v[74:75] neg_lo:[0,1] neg_hi:[0,1]
	v_mov_b32_e32 v83, v76
	v_mov_b32_e32 v82, v80
	v_mov_b32_e32 v93, v66
	v_pk_add_f32 v[78:79], v[88:89], v[76:77] neg_lo:[0,1] neg_hi:[0,1]
	v_pk_add_f32 v[2:3], v[2:3], v[82:83] neg_lo:[0,1] neg_hi:[0,1]
	v_mov_b32_e32 v75, v84
	v_pk_add_f32 v[66:67], v[92:93], v[80:81] neg_lo:[0,1] neg_hi:[0,1]
	v_pk_add_f32 v[2:3], v[74:75], v[2:3] neg_lo:[0,1] neg_hi:[0,1]
	v_mov_b32_e32 v74, v66
	v_mov_b32_e32 v75, v78
	v_pk_add_f32 v[2:3], v[74:75], v[2:3]
	v_mov_b32_e32 v78, v67
	v_pk_add_f32 v[2:3], v[2:3], v[78:79]
	v_exp_f32_e32 v0, v0
	v_pk_add_f32 v[2:3], v[70:71], v[2:3]
	v_add_f32_e32 v0, 1.0, v0
	v_cndmask_b32_e32 v2, v209, v2, vcc
	v_cmp_neq_f32_e32 vcc, s27, v102
	v_rcp_f32_e32 v0, v0
	s_nop 0
	v_cndmask_b32_e32 v3, v209, v3, vcc
	v_cmp_lt_f32_e64 vcc, |v128|, s39
	v_cndmask_b32_e64 v3, v3, v102, s[0:1]
	s_nop 0
	v_cndmask_b32_e32 v2, v2, v128, vcc
	v_pk_mul_f32 v[60:61], v[60:61], v[2:3]
	s_nop 0
	v_mul_f32_e32 v13, 0x3fb8aa3b, v61
	v_exp_f32_e32 v74, v13
	v_pk_add_f32 v[66:67], v[60:61], v[60:61]
	v_fma_f32 v13, -v74, v74, 1.0
	v_fmamk_f32 v25, v67, 0x3d2aaaab, v196
	v_fma_f32 v25, v67, v25, 0.5
	v_fma_f32 v25, v67, v25, 1.0
	v_mul_f32_e64 v25, v25, -v67
	v_cmp_lt_f32_e64 s[0:1], s40, v67
	v_cmp_lt_f32_e32 vcc, s40, v66
	s_nop 0
	v_cndmask_b32_e64 v13, v13, v25, s[0:1]
	v_max_f32_e32 v13, 0, v13
	v_sqrt_f32_e32 v13, v13
	v_fmamk_f32 v25, v66, 0x3d2aaaab, v196
	v_fma_f32 v25, v66, v25, 0.5
	v_fma_f32 v25, v66, v25, 1.0
	v_mul_f32_e32 v13, v137, v13
	v_mul_f32_e32 v75, v13, v130
	v_mul_f32_e32 v13, 0x3fb8aa3b, v60
	v_exp_f32_e32 v76, v13
	v_mul_f32_e64 v25, v25, -v66
	v_fma_f32 v13, -v76, v76, 1.0
	v_cndmask_b32_e32 v13, v13, v25, vcc
	v_max_f32_e32 v13, 0, v13
	v_sqrt_f32_e32 v13, v13
	s_nop 0
	v_mul_f32_e32 v13, v136, v13
	v_mul_f32_e32 v77, v13, v96
	global_store_dwordx4 v[58:59], v[74:77], off offset:16
	v_add_co_u32_e32 v58, vcc, s66, v72
	v_pk_mul_f32 v[48:49], v[48:49], s[44:45] op_sel_hi:[1,0]
	s_nop 0
	v_addc_co_u32_e32 v59, vcc, 0, v73, vcc
	global_load_dwordx2 v[66:67], v[58:59], off offset:32
	v_pk_mul_f32 v[48:49], v[48:49], v[2:3]
	s_nop 0
	v_mul_f32_e32 v13, 0x3fb8aa3b, v49
	v_exp_f32_e32 v58, v13
	v_pk_add_f32 v[70:71], v[48:49], v[48:49]
	v_mul_f32_e32 v27, 0x3fb8aa3b, v48
	v_fmamk_f32 v25, v71, 0x3d2aaaab, v196
	v_exp_f32_e32 v60, v27
	v_fma_f32 v25, v71, v25, 0.5
	v_fmamk_f32 v27, v70, 0x3d2aaaab, v196
	v_fma_f32 v25, v71, v25, 1.0
	v_fma_f32 v27, v70, v27, 0.5
	v_fma_f32 v13, -v58, v58, 1.0
	v_mul_f32_e64 v25, v25, -v71
	v_cmp_lt_f32_e32 vcc, s40, v71
	v_fma_f32 v27, v70, v27, 1.0
	v_mul_f32_e64 v27, v27, -v70
	v_cndmask_b32_e32 v13, v13, v25, vcc
	v_fma_f32 v25, -v60, v60, 1.0
	v_cmp_lt_f32_e32 vcc, s40, v70
	v_max_f32_e32 v13, 0, v13
	v_sqrt_f32_e32 v13, v13
	v_cndmask_b32_e32 v25, v25, v27, vcc
	v_max_f32_e32 v25, 0, v25
	v_sqrt_f32_e32 v25, v25
	v_mul_f32_e32 v13, v133, v13
	v_mul_f32_e32 v59, v13, v132
	v_mul_f32_e32 v13, v138, v25
	v_mul_f32_e32 v61, v13, v131
	global_store_dwordx4 v[50:51], v[32:35], off
	global_store_dwordx4 v[50:51], v[58:61], off offset:16
	s_nop 0
	v_add_co_u32_e32 v32, vcc, s67, v72
	s_waitcnt vmcnt(2)
	v_lshlrev_b32_e32 v13, 16, v66
	v_addc_co_u32_e32 v33, vcc, 0, v73, vcc
	global_load_dwordx2 v[48:49], v[32:33], off offset:32
	v_pk_mul_f32 v[32:33], v[106:107], s[44:45] op_sel_hi:[1,0]
	v_mul_f32_e32 v29, v68, v13
	v_pk_mul_f32 v[34:35], v[32:33], v[2:3]
	v_and_b32_e32 v25, 0xffff0000, v66
	v_mul_f32_e32 v13, 0x3fb8aa3b, v35
	v_exp_f32_e32 v32, v13
	v_pk_add_f32 v[50:51], v[34:35], v[34:35]
	v_mul_f32_e32 v31, v69, v25
	v_fmamk_f32 v25, v51, 0x3d2aaaab, v196
	v_fma_f32 v25, v51, v25, 0.5
	v_fma_f32 v25, v51, v25, 1.0
	v_fma_f32 v13, -v32, v32, 1.0
	v_mul_f32_e64 v25, v25, -v51
	v_cmp_lt_f32_e64 s[0:1], s40, v51
	v_lshlrev_b32_e32 v27, 16, v67
	v_cmp_lt_f32_e32 vcc, s40, v50
	v_cndmask_b32_e64 v13, v13, v25, s[0:1]
	v_max_f32_e32 v13, 0, v13
	v_sqrt_f32_e32 v13, v13
	v_fmamk_f32 v25, v50, 0x3d2aaaab, v196
	v_fma_f32 v25, v50, v25, 0.5
	v_fma_f32 v25, v50, v25, 1.0
	v_mul_f32_e32 v13, v139, v13
	v_mul_f32_e32 v33, v13, v27
	v_mul_f32_e32 v13, 0x3fb8aa3b, v34
	v_exp_f32_e32 v34, v13
	v_mul_f32_e64 v25, v25, -v50
	v_and_b32_e32 v58, 0xffff0000, v67
	v_fma_f32 v13, -v34, v34, 1.0
	v_cndmask_b32_e32 v13, v13, v25, vcc
	v_max_f32_e32 v13, 0, v13
	v_sqrt_f32_e32 v13, v13
	s_nop 0
	v_mul_f32_e32 v13, v124, v13
	v_mul_f32_e32 v35, v13, v58
	global_store_dwordx4 v[40:41], v[28:31], off
	global_store_dwordx4 v[40:41], v[32:35], off offset:16
	s_nop 0
	v_add_co_u32_e32 v28, vcc, s22, v72
	s_waitcnt vmcnt(2)
	v_lshlrev_b32_e32 v13, 16, v48
	v_addc_co_u32_e32 v29, vcc, 0, v73, vcc
	global_load_dwordx2 v[32:33], v[28:29], off offset:32
	v_pk_mul_f32 v[28:29], v[62:63], s[44:45] op_sel_hi:[1,0]
	v_mul_f32_e32 v25, v64, v13
	v_pk_mul_f32 v[30:31], v[28:29], v[2:3]
	v_lshlrev_b32_e32 v40, 16, v49
	v_mul_f32_e32 v13, 0x3fb8aa3b, v31
	v_exp_f32_e32 v28, v13
	v_pk_add_f32 v[34:35], v[30:31], v[30:31]
	v_and_b32_e32 v27, 0xffff0000, v48
	v_fmamk_f32 v29, v35, 0x3d2aaaab, v196
	v_fma_f32 v29, v35, v29, 0.5
	v_fma_f32 v29, v35, v29, 1.0
	v_fma_f32 v13, -v28, v28, 1.0
	v_mul_f32_e64 v29, v29, -v35
	v_cmp_lt_f32_e64 s[0:1], s40, v35
	v_fmamk_f32 v31, v34, 0x3d2aaaab, v196
	v_fma_f32 v31, v34, v31, 0.5
	v_cndmask_b32_e64 v13, v13, v29, s[0:1]
	v_max_f32_e32 v13, 0, v13
	v_sqrt_f32_e32 v13, v13
	v_fma_f32 v31, v34, v31, 1.0
	v_cmp_lt_f32_e32 vcc, s40, v34
	v_mul_f32_e64 v31, v31, -v34
	v_mul_f32_e32 v13, v140, v13
	v_mul_f32_e32 v29, v13, v40
	v_mul_f32_e32 v13, 0x3fb8aa3b, v30
	v_exp_f32_e32 v30, v13
	v_and_b32_e32 v41, 0xffff0000, v49
	v_mul_f32_e32 v27, v65, v27
	v_fma_f32 v13, -v30, v30, 1.0
	v_cndmask_b32_e32 v13, v13, v31, vcc
	v_max_f32_e32 v13, 0, v13
	v_sqrt_f32_e32 v13, v13
	s_nop 0
	v_mul_f32_e32 v13, v125, v13
	v_mul_f32_e32 v31, v13, v41
	global_store_dwordx4 v[38:39], v[24:27], off
	global_store_dwordx4 v[38:39], v[28:31], off offset:16
	s_nop 0
	v_add_co_u32_e32 v24, vcc, s41, v72
	s_waitcnt vmcnt(2)
	v_lshlrev_b32_e32 v13, 16, v32
	v_addc_co_u32_e32 v25, vcc, 0, v73, vcc
	global_load_dwordx2 v[28:29], v[24:25], off offset:32
	v_and_b32_e32 v24, 0xffff0000, v32
	v_mul_f32_e32 v23, v23, v24
	v_pk_mul_f32 v[24:25], v[54:55], s[44:45] op_sel_hi:[1,0]
	v_mul_f32_e32 v21, v21, v13
	v_pk_mul_f32 v[26:27], v[24:25], v[2:3]
	v_lshlrev_b32_e32 v32, 16, v33
	v_mul_f32_e32 v13, 0x3fb8aa3b, v27
	v_exp_f32_e32 v24, v13
	v_pk_add_f32 v[30:31], v[26:27], v[26:27]
	v_and_b32_e32 v33, 0xffff0000, v33
	v_fmamk_f32 v25, v31, 0x3d2aaaab, v196
	v_fma_f32 v25, v31, v25, 0.5
	v_fma_f32 v25, v31, v25, 1.0
	v_fma_f32 v13, -v24, v24, 1.0
	v_mul_f32_e64 v25, v25, -v31
	v_cmp_lt_f32_e64 s[0:1], s40, v31
	v_fmamk_f32 v27, v30, 0x3d2aaaab, v196
	v_fma_f32 v27, v30, v27, 0.5
	v_cndmask_b32_e64 v13, v13, v25, s[0:1]
	v_max_f32_e32 v13, 0, v13
	v_sqrt_f32_e32 v13, v13
	v_fma_f32 v27, v30, v27, 1.0
	v_cmp_lt_f32_e32 vcc, s40, v30
	v_mul_f32_e64 v27, v27, -v30
	v_mul_f32_e32 v13, v141, v13
	v_mul_f32_e32 v25, v13, v32
	v_mul_f32_e32 v13, 0x3fb8aa3b, v26
	v_exp_f32_e32 v26, v13
	s_nop 0
	v_fma_f32 v13, -v26, v26, 1.0
	v_cndmask_b32_e32 v13, v13, v27, vcc
	v_max_f32_e32 v13, 0, v13
	v_sqrt_f32_e32 v13, v13
	s_nop 0
	v_mul_f32_e32 v13, v126, v13
	v_mul_f32_e32 v27, v13, v33
	global_store_dwordx4 v[42:43], v[20:23], off
	global_store_dwordx4 v[42:43], v[24:27], off offset:16
	s_nop 0
	v_add_co_u32_e32 v20, vcc, s23, v72
	s_waitcnt vmcnt(2)
	v_lshlrev_b32_e32 v13, 16, v28
	v_addc_co_u32_e32 v21, vcc, 0, v73, vcc
	global_load_dwordx2 v[24:25], v[20:21], off offset:32
	v_and_b32_e32 v20, 0xffff0000, v28
	v_mul_f32_e32 v19, v19, v20
	v_pk_mul_f32 v[20:21], v[52:53], s[44:45] op_sel_hi:[1,0]
	v_mul_f32_e32 v17, v17, v13
	v_pk_mul_f32 v[22:23], v[20:21], v[2:3]
	v_lshlrev_b32_e32 v28, 16, v29
	v_mul_f32_e32 v13, 0x3fb8aa3b, v23
	v_exp_f32_e32 v20, v13
	v_pk_add_f32 v[26:27], v[22:23], v[22:23]
	v_and_b32_e32 v29, 0xffff0000, v29
	v_fmamk_f32 v21, v27, 0x3d2aaaab, v196
	v_fma_f32 v21, v27, v21, 0.5
	v_fma_f32 v21, v27, v21, 1.0
	v_fma_f32 v13, -v20, v20, 1.0
	v_mul_f32_e64 v21, v21, -v27
	v_cmp_lt_f32_e64 s[0:1], s40, v27
	v_fmamk_f32 v23, v26, 0x3d2aaaab, v196
	v_fma_f32 v23, v26, v23, 0.5
	v_cndmask_b32_e64 v13, v13, v21, s[0:1]
	v_max_f32_e32 v13, 0, v13
	v_sqrt_f32_e32 v13, v13
	v_fma_f32 v23, v26, v23, 1.0
	v_cmp_lt_f32_e32 vcc, s40, v26
	v_mul_f32_e64 v23, v23, -v26
	v_mul_f32_e32 v13, v142, v13
	v_mul_f32_e32 v21, v13, v28
	v_mul_f32_e32 v13, 0x3fb8aa3b, v22
	v_exp_f32_e32 v22, v13
	s_nop 0
	v_fma_f32 v13, -v22, v22, 1.0
	v_cndmask_b32_e32 v13, v13, v23, vcc
	v_max_f32_e32 v13, 0, v13
	v_sqrt_f32_e32 v13, v13
	s_nop 0
	v_mul_f32_e32 v13, v127, v13
	v_mul_f32_e32 v23, v13, v29
	global_store_dwordx4 v[44:45], v[16:19], off
	global_store_dwordx4 v[44:45], v[20:23], off offset:16
	s_nop 0
	v_add_co_u32_e32 v16, vcc, s42, v72
	s_waitcnt vmcnt(2)
	v_lshlrev_b32_e32 v13, 16, v24
	v_addc_co_u32_e32 v17, vcc, 0, v73, vcc
	global_load_dwordx2 v[20:21], v[16:17], off offset:32
	v_and_b32_e32 v16, 0xffff0000, v24
	v_mul_f32_e32 v11, v11, v16
	v_pk_mul_f32 v[16:17], v[46:47], s[44:45] op_sel_hi:[1,0]
	v_mul_f32_e32 v9, v9, v13
	v_pk_mul_f32 v[18:19], v[16:17], v[2:3]
	v_lshlrev_b32_e32 v24, 16, v25
	v_mul_f32_e32 v13, 0x3fb8aa3b, v19
	v_exp_f32_e32 v16, v13
	v_pk_add_f32 v[22:23], v[18:19], v[18:19]
	v_and_b32_e32 v25, 0xffff0000, v25
	v_fmamk_f32 v17, v23, 0x3d2aaaab, v196
	v_fma_f32 v17, v23, v17, 0.5
	v_fma_f32 v17, v23, v17, 1.0
	v_fma_f32 v13, -v16, v16, 1.0
	v_mul_f32_e64 v17, v17, -v23
	v_cmp_lt_f32_e64 s[0:1], s40, v23
	v_fmamk_f32 v19, v22, 0x3d2aaaab, v196
	v_fma_f32 v19, v22, v19, 0.5
	v_cndmask_b32_e64 v13, v13, v17, s[0:1]
	v_max_f32_e32 v13, 0, v13
	v_sqrt_f32_e32 v13, v13
	v_fma_f32 v19, v22, v19, 1.0
	v_cmp_lt_f32_e32 vcc, s40, v22
	v_mul_f32_e64 v19, v19, -v22
	v_mul_f32_e32 v13, v134, v13
	v_mul_f32_e32 v17, v13, v24
	v_mul_f32_e32 v13, 0x3fb8aa3b, v18
	v_exp_f32_e32 v18, v13
	s_nop 0
	v_fma_f32 v13, -v18, v18, 1.0
	v_cndmask_b32_e32 v13, v13, v19, vcc
	v_max_f32_e32 v13, 0, v13
	v_sqrt_f32_e32 v13, v13
	s_nop 0
	v_mul_f32_e32 v13, v15, v13
	v_mul_f32_e32 v19, v13, v25
	global_store_dwordx4 v[36:37], v[8:11], off
	global_store_dwordx4 v[36:37], v[16:19], off offset:16
	v_pk_mul_f32 v[0:1], v[0:1], s[44:45] op_sel_hi:[1,0]
	s_waitcnt vmcnt(2)
	v_lshlrev_b32_e32 v8, 16, v20
	v_pk_mul_f32 v[2:3], v[0:1], v[2:3]
	v_mul_f32_e32 v13, v5, v8
	v_pk_add_f32 v[8:9], v[2:3], v[2:3]
	v_mul_f32_e32 v0, 0x3fb8aa3b, v3
	v_fmamk_f32 v3, v9, 0x3d2aaaab, v196
	v_exp_f32_e32 v0, v0
	v_fma_f32 v3, v9, v3, 0.5
	v_mul_f32_e32 v2, 0x3fb8aa3b, v2
	v_fma_f32 v3, v9, v3, 1.0
	v_exp_f32_e32 v2, v2
	v_mul_f32_e64 v3, v3, -v9
	v_cmp_lt_f32_e32 vcc, s40, v9
	v_fmamk_f32 v9, v8, 0x3d2aaaab, v196
	v_fma_f32 v9, v8, v9, 0.5
	v_fma_f32 v5, -v0, v0, 1.0
	v_fma_f32 v9, v8, v9, 1.0
	v_cndmask_b32_e32 v3, v5, v3, vcc
	v_fma_f32 v5, -v2, v2, 1.0
	v_mul_f32_e64 v9, v9, -v8
	v_cmp_lt_f32_e32 vcc, s40, v8
	v_max_f32_e32 v3, 0, v3
	v_sqrt_f32_e32 v3, v3
	v_cndmask_b32_e32 v5, v5, v9, vcc
	v_max_f32_e32 v5, 0, v5
	v_sqrt_f32_e32 v5, v5
	v_and_b32_e32 v10, 0xffff0000, v20
	v_lshlrev_b32_e32 v1, 16, v21
	v_mul_f32_e32 v3, v6, v3
	v_or3_b32 v56, v56, v122, v146
	v_and_b32_e32 v11, 0xffff0000, v21
	v_mul_f32_e32 v15, v4, v10
	v_mul_f32_e32 v1, v3, v1
	v_mul_f32_e32 v3, v7, v5
	v_lshl_add_u64 v[4:5], v[56:57], 3, s[14:15]
	v_mul_f32_e32 v3, v3, v11
	global_store_dwordx4 v[4:5], v[12:15], off
	global_store_dwordx4 v[4:5], v[0:3], off offset:16
	s_mov_b64 s[22:23], s[20:21]
	v_readlane_b32 s68, v253, 18
	v_readlane_b32 s75, v253, 20
	s_barrier
	s_cmpk_gt_i32 s36, 0x1ff
	s_cbranch_scc0 .LBB0_741
	s_branch .LBB0_761

.LBB0_788:
	s_ashr_i32 s29, s28, 31
	s_lshl_b64 s[28:29], s[28:29], 20
	s_add_u32 s28, s35, s28
	s_addc_u32 s29, s36, s29
	s_ashr_i32 s27, s26, 31
	v_lshlrev_b32_e32 v3, 6, v1
	s_lshl_b64 s[26:27], s[26:27], 20
	v_and_b32_e32 v2, 48, v1
	v_and_b32_e32 v4, 0x3c0, v3
	v_lshlrev_b32_e32 v1, 2, v1
	s_add_u32 s30, s10, s26
	v_or_b32_e32 v5, v4, v2
	v_and_b32_e32 v1, 32, v1
	v_lshlrev_b32_e32 v0, 13, v0
	s_mov_b32 s26, 0x18000
	v_and_b32_e32 v135, 0x6000, v0
	v_bitop3_b32 v0, v5, s26, v1 bitop3:0xde
	s_mov_b32 s26, 0x10400
	s_addc_u32 s31, s11, s27
	v_bitop3_b32 v149, v5, s26, v1 bitop3:0xde
	s_add_i32 s26, s55, s58
	s_ashr_i32 s27, s26, 31
	s_waitcnt vmcnt(0)
	s_add_i32 s47, s1, 0x10000
	s_add_i32 s48, s1, 0x18000
	s_add_i32 s49, s1, 0x12000
	s_add_i32 s50, s1, 0x1a000
	s_add_i32 s51, s1, 0x14000
	s_add_i32 s52, s1, 0x1c000
	s_add_i32 s53, s1, 0x16000
	s_add_i32 s54, s1, 0x1e000
	s_lshl_b64 s[26:27], s[26:27], 20
	v_bitop3_b32 v134, v4, v1, v2 bitop3:0x36
	v_and_b32_e32 v136, 0xffffc000, v3
	s_add_u32 s55, s6, s26
	v_mov_b32_e32 v4, 0
	v_or_b32_e32 v137, 0x800, v136
	v_or_b32_e32 v138, 0x1000, v136
	v_or_b32_e32 v139, 0x1800, v136
	v_or_b32_e32 v140, 0x2000, v136
	v_or_b32_e32 v141, 0x2800, v136
	v_or_b32_e32 v142, 0x3000, v136
	v_or_b32_e32 v143, 0x3800, v136
	v_bitop3_b32 v145, v5, s33, v1 bitop3:0xde
	s_addc_u32 s58, s7, s27
	s_mov_b64 s[26:27], 0
	s_mov_b32 s62, 1
	v_add_u32_e32 v150, v0, v135
	v_mov_b32_e32 v5, v4
	v_mov_b32_e32 v6, v4
	v_mov_b32_e32 v7, v4
	v_mov_b32_e32 v12, v4
	v_mov_b32_e32 v13, v4
	v_mov_b32_e32 v14, v4
	v_mov_b32_e32 v15, v4
	v_mov_b32_e32 v16, v4
	v_mov_b32_e32 v17, v4
	v_mov_b32_e32 v18, v4
	v_mov_b32_e32 v19, v4
	v_mov_b32_e32 v20, v4
	v_mov_b32_e32 v21, v4
	v_mov_b32_e32 v22, v4
	v_mov_b32_e32 v23, v4
	v_mov_b32_e32 v24, v4
	v_mov_b32_e32 v25, v4
	v_mov_b32_e32 v26, v4
	v_mov_b32_e32 v27, v4
	v_mov_b32_e32 v28, v4
	v_mov_b32_e32 v29, v4
	v_mov_b32_e32 v30, v4
	v_mov_b32_e32 v31, v4
	v_mov_b32_e32 v32, v4
	v_mov_b32_e32 v33, v4
	v_mov_b32_e32 v34, v4
	v_mov_b32_e32 v35, v4
	v_mov_b32_e32 v36, v4
	v_mov_b32_e32 v37, v4
	v_mov_b32_e32 v38, v4
	v_mov_b32_e32 v39, v4
	v_mov_b32_e32 v40, v4
	v_mov_b32_e32 v41, v4
	v_mov_b32_e32 v42, v4
	v_mov_b32_e32 v43, v4
	v_mov_b32_e32 v44, v4
	v_mov_b32_e32 v45, v4
	v_mov_b32_e32 v46, v4
	v_mov_b32_e32 v47, v4
	v_mov_b32_e32 v48, v4
	v_mov_b32_e32 v49, v4
	v_mov_b32_e32 v50, v4
	v_mov_b32_e32 v51, v4
	v_mov_b32_e32 v52, v4
	v_mov_b32_e32 v53, v4
	v_mov_b32_e32 v54, v4
	v_mov_b32_e32 v55, v4
	v_mov_b32_e32 v56, v4
	v_mov_b32_e32 v57, v4
	v_mov_b32_e32 v58, v4
	v_mov_b32_e32 v59, v4
	v_mov_b32_e32 v60, v4
	v_mov_b32_e32 v61, v4
	v_mov_b32_e32 v62, v4
	v_mov_b32_e32 v63, v4
	v_mov_b32_e32 v64, v4
	v_mov_b32_e32 v65, v4
	v_mov_b32_e32 v66, v4
	v_mov_b32_e32 v67, v4
	v_mov_b32_e32 v68, v4
	v_mov_b32_e32 v69, v4
	v_mov_b32_e32 v70, v4
	v_mov_b32_e32 v71, v4
	v_mov_b32_e32 v72, v4
	v_mov_b32_e32 v73, v4
	v_mov_b32_e32 v74, v4
	v_mov_b32_e32 v75, v4
	v_mov_b32_e32 v76, v4
	v_mov_b32_e32 v77, v4
	v_mov_b32_e32 v78, v4
	v_mov_b32_e32 v79, v4
	v_mov_b32_e32 v80, v4
	v_mov_b32_e32 v81, v4
	v_mov_b32_e32 v82, v4
	v_mov_b32_e32 v83, v4
	v_mov_b32_e32 v84, v4
	v_mov_b32_e32 v85, v4
	v_mov_b32_e32 v86, v4
	v_mov_b32_e32 v87, v4
	v_mov_b32_e32 v88, v4
	v_mov_b32_e32 v89, v4
	v_mov_b32_e32 v90, v4
	v_mov_b32_e32 v91, v4
	v_mov_b32_e32 v92, v4
	v_mov_b32_e32 v93, v4
	v_mov_b32_e32 v94, v4
	v_mov_b32_e32 v95, v4
	v_mov_b32_e32 v96, v4
	v_mov_b32_e32 v97, v4
	v_mov_b32_e32 v98, v4
	v_mov_b32_e32 v99, v4
	v_mov_b32_e32 v100, v4
	v_mov_b32_e32 v101, v4
	v_mov_b32_e32 v102, v4
	v_mov_b32_e32 v103, v4
	v_mov_b32_e32 v104, v4
	v_mov_b32_e32 v105, v4
	v_mov_b32_e32 v106, v4
	v_mov_b32_e32 v107, v4
	v_mov_b32_e32 v108, v4
	v_mov_b32_e32 v109, v4
	v_mov_b32_e32 v110, v4
	v_mov_b32_e32 v111, v4
	v_mov_b32_e32 v112, v4
	v_mov_b32_e32 v113, v4
	v_mov_b32_e32 v114, v4
	v_mov_b32_e32 v115, v4
	v_mov_b32_e32 v116, v4
	v_mov_b32_e32 v117, v4
	v_mov_b32_e32 v118, v4
	v_mov_b32_e32 v119, v4
	v_mov_b32_e32 v120, v4
	v_mov_b32_e32 v121, v4
	v_mov_b32_e32 v122, v4
	v_mov_b32_e32 v123, v4
	v_mov_b32_e32 v124, v4
	v_mov_b32_e32 v125, v4
	v_mov_b32_e32 v126, v4
	v_mov_b32_e32 v127, v4
	v_mov_b32_e32 v8, v4
	v_mov_b32_e32 v9, v4
	v_mov_b32_e32 v10, v4
	v_mov_b32_e32 v11, v4
	v_mov_b32_e32 v0, v4
	v_mov_b32_e32 v1, v4
	v_mov_b32_e32 v2, v4
	v_mov_b32_e32 v3, v4
	s_waitcnt lgkmcnt(0)
	s_barrier
	s_add_u32 s63, s55, s26
	s_addc_u32 s70, s58, s27
	s_add_u32 s64, s63, 0x1b900080
	s_addc_u32 s65, s70, 0
	s_add_u32 s71, s2, s26
	s_addc_u32 s72, s3, s27
	s_add_u32 s68, s71, 0x80
	s_addc_u32 s69, s72, 0
	v_add_u32_e32 v151, v134, v135
	v_add_u32_e32 v189, v134, v136
	ds_read_b128 v[152:155], v151 offset:32768
	ds_read_b128 v[156:159], v189
	ds_read_b128 v[160:163], v151 offset:34816
	ds_read_b128 v[164:167], v189 offset:2048
	ds_read_b128 v[168:171], v151 offset:36864
	ds_read_b128 v[172:175], v151 offset:38912
	ds_read_b128 v[176:179], v189 offset:4096
	ds_read_b128 v[180:183], v189 offset:6144
	s_branch .Lmy_rot_789
.LBB0_789:
	s_add_u32 s63, s55, s26
	s_addc_u32 s70, s58, s27
	s_add_u32 s64, s63, 0x1b900080
	s_addc_u32 s65, s70, 0
	s_add_u32 s71, s2, s26
	s_addc_u32 s72, s3, s27
	s_add_u32 s68, s71, 0x80
	s_addc_u32 s69, s72, 0
	v_add_u32_e32 v151, v134, v135
	v_add_u32_e32 v189, v134, v136
	ds_read_b128 v[152:155], v151 offset:32768
	ds_read_b128 v[156:159], v189
	v_mfma_f32_16x16x32_bf16 v[28:31], v[160:163], v[176:179], v[28:31]
	v_mfma_f32_16x16x32_bf16 v[12:15], v[160:163], v[180:183], v[12:15]
	ds_read_b128 v[160:163], v151 offset:34816
	v_mfma_f32_16x16x32_bf16 v[24:27], v[164:167], v[176:179], v[24:27]
	v_mfma_f32_16x16x32_bf16 v[4:7], v[164:167], v[180:183], v[4:7]
	ds_read_b128 v[164:167], v189 offset:2048
	v_mfma_f32_16x16x32_bf16 v[20:23], v[168:171], v[176:179], v[20:23]
	v_mfma_f32_16x16x32_bf16 v[8:11], v[168:171], v[180:183], v[8:11]
	ds_read_b128 v[168:171], v151 offset:36864
	v_mfma_f32_16x16x32_bf16 v[16:19], v[172:175], v[176:179], v[16:19]
	v_mfma_f32_16x16x32_bf16 v[0:3], v[172:175], v[180:183], v[0:3]
	ds_read_b128 v[172:175], v151 offset:38912
	ds_read_b128 v[176:179], v189 offset:4096
	ds_read_b128 v[180:183], v189 offset:6144
.Lmy_rot_789:
	s_waitcnt lgkmcnt(6)
	v_mfma_f32_16x16x32_bf16 v[124:127], v[152:155], v[156:159], v[124:127]
	s_waitcnt lgkmcnt(5)
	v_mfma_f32_16x16x32_bf16 v[120:123], v[160:163], v[156:159], v[120:123]
	s_waitcnt lgkmcnt(4)
	s_mov_b32 m0, s47
	v_mfma_f32_16x16x32_bf16 v[108:111], v[152:155], v[164:167], v[108:111]
	global_load_lds_dwordx4 v128, s[64:65]
	v_mfma_f32_16x16x32_bf16 v[104:107], v[160:163], v[164:167], v[104:107]
	s_waitcnt lgkmcnt(3)
	v_mfma_f32_16x16x32_bf16 v[116:119], v[168:171], v[156:159], v[116:119]
	v_mfma_f32_16x16x32_bf16 v[100:103], v[168:171], v[164:167], v[100:103]
	s_waitcnt lgkmcnt(2)
	s_mov_b32 m0, s48
	v_mfma_f32_16x16x32_bf16 v[112:115], v[172:175], v[156:159], v[112:115]
	global_load_lds_dwordx4 v128, s[68:69]
	ds_read_b128 v[156:159], v189 offset:8192
	v_mfma_f32_16x16x32_bf16 v[96:99], v[172:175], v[164:167], v[96:99]
	ds_read_b128 v[164:167], v189 offset:10240
	s_waitcnt lgkmcnt(3)
	v_mfma_f32_16x16x32_bf16 v[92:95], v[152:155], v[176:179], v[92:95]
	v_mfma_f32_16x16x32_bf16 v[88:91], v[160:163], v[176:179], v[88:91]
	s_mov_b32 m0, s49
	v_mfma_f32_16x16x32_bf16 v[84:87], v[168:171], v[176:179], v[84:87]
	global_load_lds_dwordx4 v130, s[64:65]
	v_mfma_f32_16x16x32_bf16 v[80:83], v[172:175], v[176:179], v[80:83]
	ds_read_b128 v[176:179], v189 offset:12288
	s_waitcnt lgkmcnt(3)
	v_mfma_f32_16x16x32_bf16 v[76:79], v[152:155], v[180:183], v[76:79]
	v_mfma_f32_16x16x32_bf16 v[72:75], v[160:163], v[180:183], v[72:75]
	s_mov_b32 m0, s50
	v_mfma_f32_16x16x32_bf16 v[68:71], v[168:171], v[180:183], v[68:71]
	global_load_lds_dwordx4 v130, s[68:69]
	v_mfma_f32_16x16x32_bf16 v[64:67], v[172:175], v[180:183], v[64:67]
	ds_read_b128 v[180:183], v189 offset:14336
	s_waitcnt lgkmcnt(3)
	v_mfma_f32_16x16x32_bf16 v[56:59], v[160:163], v[156:159], v[56:59]
	s_waitcnt lgkmcnt(2)
	v_mfma_f32_16x16x32_bf16 v[40:43], v[160:163], v[164:167], v[40:43]
	s_waitcnt lgkmcnt(1)
	s_mov_b32 m0, s51
	v_mfma_f32_16x16x32_bf16 v[24:27], v[160:163], v[176:179], v[24:27]
	global_load_lds_dwordx4 v132, s[64:65]
	s_waitcnt lgkmcnt(0)
	v_mfma_f32_16x16x32_bf16 v[4:7], v[160:163], v[180:183], v[4:7]
	ds_read_b128 v[160:163], v151 offset:33792
	v_mfma_f32_16x16x32_bf16 v[60:63], v[152:155], v[156:159], v[60:63]
	v_mfma_f32_16x16x32_bf16 v[44:47], v[152:155], v[164:167], v[44:47]
	s_mov_b32 m0, s52
	v_mfma_f32_16x16x32_bf16 v[28:31], v[152:155], v[176:179], v[28:31]
	global_load_lds_dwordx4 v132, s[68:69]
	v_mfma_f32_16x16x32_bf16 v[12:15], v[152:155], v[180:183], v[12:15]
	ds_read_b128 v[152:155], v189 offset:1024
	v_mfma_f32_16x16x32_bf16 v[36:39], v[168:171], v[164:167], v[36:39]
	v_mfma_f32_16x16x32_bf16 v[32:35], v[172:175], v[164:167], v[32:35]
	ds_read_b128 v[164:167], v151 offset:35840
	s_mov_b32 m0, s53
	v_mfma_f32_16x16x32_bf16 v[52:55], v[168:171], v[156:159], v[52:55]
	global_load_lds_dwordx4 v146, s[64:65]
	v_mfma_f32_16x16x32_bf16 v[48:51], v[172:175], v[156:159], v[48:51]
	ds_read_b128 v[156:159], v189 offset:3072
	v_mfma_f32_16x16x32_bf16 v[20:23], v[168:171], v[176:179], v[20:23]
	v_mfma_f32_16x16x32_bf16 v[16:19], v[172:175], v[176:179], v[16:19]
	ds_read_b128 v[176:179], v189 offset:5120
	s_mov_b32 m0, s54
	v_mfma_f32_16x16x32_bf16 v[8:11], v[168:171], v[180:183], v[8:11]
	global_load_lds_dwordx4 v146, s[68:69]
	ds_read_b128 v[168:171], v151 offset:37888
	v_mfma_f32_16x16x32_bf16 v[0:3], v[172:175], v[180:183], v[0:3]
	ds_read_b128 v[172:175], v151 offset:39936
	ds_read_b128 v[180:183], v189 offset:7168
	s_waitcnt lgkmcnt(6)
	v_mfma_f32_16x16x32_bf16 v[124:127], v[160:163], v[152:155], v[124:127]
	s_waitcnt lgkmcnt(5)
	v_mfma_f32_16x16x32_bf16 v[120:123], v[164:167], v[152:155], v[120:123]
	s_waitcnt lgkmcnt(4)
	v_mfma_f32_16x16x32_bf16 v[108:111], v[160:163], v[156:159], v[108:111]
	v_mfma_f32_16x16x32_bf16 v[104:107], v[164:167], v[156:159], v[104:107]
	s_waitcnt lgkmcnt(3)
	v_mfma_f32_16x16x32_bf16 v[92:95], v[160:163], v[176:179], v[92:95]
	v_mfma_f32_16x16x32_bf16 v[88:91], v[164:167], v[176:179], v[88:91]
	s_waitcnt lgkmcnt(2)
	v_mfma_f32_16x16x32_bf16 v[116:119], v[168:171], v[152:155], v[116:119]
	s_waitcnt lgkmcnt(1)
	v_mfma_f32_16x16x32_bf16 v[112:115], v[172:175], v[152:155], v[112:115]
	ds_read_b128 v[152:155], v189 offset:9216
	v_mfma_f32_16x16x32_bf16 v[100:103], v[168:171], v[156:159], v[100:103]
	v_mfma_f32_16x16x32_bf16 v[96:99], v[172:175], v[156:159], v[96:99]
	ds_read_b128 v[156:159], v189 offset:11264
	v_mfma_f32_16x16x32_bf16 v[84:87], v[168:171], v[176:179], v[84:87]
	v_mfma_f32_16x16x32_bf16 v[80:83], v[172:175], v[176:179], v[80:83]
	ds_read_b128 v[176:179], v189 offset:13312
	s_waitcnt lgkmcnt(3)
	v_mfma_f32_16x16x32_bf16 v[76:79], v[160:163], v[180:183], v[76:79]
	v_mfma_f32_16x16x32_bf16 v[72:75], v[164:167], v[180:183], v[72:75]
	v_mfma_f32_16x16x32_bf16 v[68:71], v[168:171], v[180:183], v[68:71]
	v_mfma_f32_16x16x32_bf16 v[64:67], v[172:175], v[180:183], v[64:67]
	ds_read_b128 v[180:183], v189 offset:15360
	s_waitcnt lgkmcnt(3)
	v_mfma_f32_16x16x32_bf16 v[60:63], v[160:163], v[152:155], v[60:63]
	v_mfma_f32_16x16x32_bf16 v[56:59], v[164:167], v[152:155], v[56:59]
	v_mfma_f32_16x16x32_bf16 v[52:55], v[168:171], v[152:155], v[52:55]
	v_mfma_f32_16x16x32_bf16 v[48:51], v[172:175], v[152:155], v[48:51]
	s_waitcnt lgkmcnt(2)
	v_mfma_f32_16x16x32_bf16 v[44:47], v[160:163], v[156:159], v[44:47]
	v_mfma_f32_16x16x32_bf16 v[40:43], v[164:167], v[156:159], v[40:43]
	v_mfma_f32_16x16x32_bf16 v[36:39], v[168:171], v[156:159], v[36:39]
	v_mfma_f32_16x16x32_bf16 v[32:35], v[172:175], v[156:159], v[32:35]
	s_add_u32 s63, s63, 0x1b900100
	s_addc_u32 s64, s70, 0
	s_add_u32 s68, s71, 0x100
	s_addc_u32 s69, s72, 0
	s_cmp_lt_u32 s62, 31
	s_cselect_b32 s65, s64, s29
	s_cselect_b32 s64, s63, s28
	s_waitcnt vmcnt(0)
	s_waitcnt lgkmcnt(0)
	s_barrier
	s_cselect_b32 s69, s69, s31
	s_cselect_b32 s68, s68, s30
	ds_read_b128 v[152:155], v150
	v_add_u32_e32 v151, v145, v136
	ds_read_b128 v[156:159], v151
	v_mfma_f32_16x16x32_bf16 v[28:31], v[160:163], v[176:179], v[28:31]
	v_mfma_f32_16x16x32_bf16 v[12:15], v[160:163], v[180:183], v[12:15]
	ds_read_b128 v[160:163], v150 offset:2048
	v_mfma_f32_16x16x32_bf16 v[24:27], v[164:167], v[176:179], v[24:27]
	v_mfma_f32_16x16x32_bf16 v[4:7], v[164:167], v[180:183], v[4:7]
	v_add_u32_e32 v151, v145, v137
	ds_read_b128 v[164:167], v151
	v_mfma_f32_16x16x32_bf16 v[20:23], v[168:171], v[176:179], v[20:23]
	v_mfma_f32_16x16x32_bf16 v[8:11], v[168:171], v[180:183], v[8:11]
	ds_read_b128 v[168:171], v150 offset:4096
	v_mfma_f32_16x16x32_bf16 v[16:19], v[172:175], v[176:179], v[16:19]
	v_mfma_f32_16x16x32_bf16 v[0:3], v[172:175], v[180:183], v[0:3]
	ds_read_b128 v[172:175], v150 offset:6144
	v_add_u32_e32 v151, v145, v138
	ds_read_b128 v[176:179], v151
	v_add_u32_e32 v151, v145, v139
	ds_read_b128 v[180:183], v151
	s_waitcnt lgkmcnt(6)
	v_mfma_f32_16x16x32_bf16 v[124:127], v[152:155], v[156:159], v[124:127]
	s_waitcnt lgkmcnt(5)
	v_mfma_f32_16x16x32_bf16 v[120:123], v[160:163], v[156:159], v[120:123]
	s_waitcnt lgkmcnt(4)
	s_mov_b32 m0, s1
	v_mfma_f32_16x16x32_bf16 v[108:111], v[152:155], v[164:167], v[108:111]
	global_load_lds_dwordx4 v128, s[64:65]
	v_mfma_f32_16x16x32_bf16 v[104:107], v[160:163], v[164:167], v[104:107]
	s_waitcnt lgkmcnt(3)
	v_mfma_f32_16x16x32_bf16 v[116:119], v[168:171], v[156:159], v[116:119]
	v_mfma_f32_16x16x32_bf16 v[100:103], v[168:171], v[164:167], v[100:103]
	s_waitcnt lgkmcnt(2)
	s_mov_b32 m0, s40
	v_mfma_f32_16x16x32_bf16 v[112:115], v[172:175], v[156:159], v[112:115]
	global_load_lds_dwordx4 v128, s[68:69]
	v_add_u32_e32 v151, v145, v140
	ds_read_b128 v[156:159], v151
	v_mfma_f32_16x16x32_bf16 v[96:99], v[172:175], v[164:167], v[96:99]
	v_add_u32_e32 v151, v145, v141
	ds_read_b128 v[164:167], v151
	s_waitcnt lgkmcnt(3)
	v_mfma_f32_16x16x32_bf16 v[92:95], v[152:155], v[176:179], v[92:95]
	v_mfma_f32_16x16x32_bf16 v[88:91], v[160:163], v[176:179], v[88:91]
	s_mov_b32 m0, s41
	v_mfma_f32_16x16x32_bf16 v[84:87], v[168:171], v[176:179], v[84:87]
	global_load_lds_dwordx4 v130, s[64:65]
	v_mfma_f32_16x16x32_bf16 v[80:83], v[172:175], v[176:179], v[80:83]
	v_add_u32_e32 v151, v145, v142
	ds_read_b128 v[176:179], v151
	s_waitcnt lgkmcnt(3)
	v_mfma_f32_16x16x32_bf16 v[76:79], v[152:155], v[180:183], v[76:79]
	v_mfma_f32_16x16x32_bf16 v[72:75], v[160:163], v[180:183], v[72:75]
	s_mov_b32 m0, s42
	v_mfma_f32_16x16x32_bf16 v[68:71], v[168:171], v[180:183], v[68:71]
	global_load_lds_dwordx4 v130, s[68:69]
	v_mfma_f32_16x16x32_bf16 v[64:67], v[172:175], v[180:183], v[64:67]
	v_add_u32_e32 v151, v145, v143
	ds_read_b128 v[180:183], v151
	s_waitcnt lgkmcnt(3)
	v_mfma_f32_16x16x32_bf16 v[56:59], v[160:163], v[156:159], v[56:59]
	s_waitcnt lgkmcnt(2)
	v_mfma_f32_16x16x32_bf16 v[40:43], v[160:163], v[164:167], v[40:43]
	s_waitcnt lgkmcnt(1)
	s_mov_b32 m0, s43
	v_mfma_f32_16x16x32_bf16 v[24:27], v[160:163], v[176:179], v[24:27]
	global_load_lds_dwordx4 v132, s[64:65]
	s_waitcnt lgkmcnt(0)
	v_mfma_f32_16x16x32_bf16 v[4:7], v[160:163], v[180:183], v[4:7]
	ds_read_b128 v[160:163], v150 offset:1024
	v_mfma_f32_16x16x32_bf16 v[60:63], v[152:155], v[156:159], v[60:63]
	v_mfma_f32_16x16x32_bf16 v[44:47], v[152:155], v[164:167], v[44:47]
	s_mov_b32 m0, s44
	v_mfma_f32_16x16x32_bf16 v[28:31], v[152:155], v[176:179], v[28:31]
	global_load_lds_dwordx4 v132, s[68:69]
	v_mfma_f32_16x16x32_bf16 v[12:15], v[152:155], v[180:183], v[12:15]
	v_add_u32_e32 v151, v149, v136
	ds_read_b128 v[152:155], v151
	v_mfma_f32_16x16x32_bf16 v[36:39], v[168:171], v[164:167], v[36:39]
	v_mfma_f32_16x16x32_bf16 v[32:35], v[172:175], v[164:167], v[32:35]
	ds_read_b128 v[164:167], v150 offset:3072
	s_mov_b32 m0, s45
	v_mfma_f32_16x16x32_bf16 v[52:55], v[168:171], v[156:159], v[52:55]
	global_load_lds_dwordx4 v146, s[64:65]
	v_mfma_f32_16x16x32_bf16 v[48:51], v[172:175], v[156:159], v[48:51]
	v_add_u32_e32 v151, v149, v137
	ds_read_b128 v[156:159], v151
	v_mfma_f32_16x16x32_bf16 v[20:23], v[168:171], v[176:179], v[20:23]
	v_mfma_f32_16x16x32_bf16 v[16:19], v[172:175], v[176:179], v[16:19]
	v_add_u32_e32 v151, v149, v138
	ds_read_b128 v[176:179], v151
	s_mov_b32 m0, s46
	v_mfma_f32_16x16x32_bf16 v[8:11], v[168:171], v[180:183], v[8:11]
	global_load_lds_dwordx4 v146, s[68:69]
	ds_read_b128 v[168:171], v150 offset:5120
	v_mfma_f32_16x16x32_bf16 v[0:3], v[172:175], v[180:183], v[0:3]
	ds_read_b128 v[172:175], v150 offset:7168
	v_add_u32_e32 v151, v149, v139
	ds_read_b128 v[180:183], v151
	s_waitcnt lgkmcnt(6)
	v_mfma_f32_16x16x32_bf16 v[124:127], v[160:163], v[152:155], v[124:127]
	s_waitcnt lgkmcnt(5)
	v_mfma_f32_16x16x32_bf16 v[120:123], v[164:167], v[152:155], v[120:123]
	s_waitcnt lgkmcnt(4)
	v_mfma_f32_16x16x32_bf16 v[108:111], v[160:163], v[156:159], v[108:111]
	v_mfma_f32_16x16x32_bf16 v[104:107], v[164:167], v[156:159], v[104:107]
	s_waitcnt lgkmcnt(3)
	v_mfma_f32_16x16x32_bf16 v[92:95], v[160:163], v[176:179], v[92:95]
	v_mfma_f32_16x16x32_bf16 v[88:91], v[164:167], v[176:179], v[88:91]
	s_waitcnt lgkmcnt(2)
	v_mfma_f32_16x16x32_bf16 v[116:119], v[168:171], v[152:155], v[116:119]
	s_waitcnt lgkmcnt(1)
	v_mfma_f32_16x16x32_bf16 v[112:115], v[172:175], v[152:155], v[112:115]
	v_add_u32_e32 v151, v149, v140
	ds_read_b128 v[152:155], v151
	v_mfma_f32_16x16x32_bf16 v[100:103], v[168:171], v[156:159], v[100:103]
	v_mfma_f32_16x16x32_bf16 v[96:99], v[172:175], v[156:159], v[96:99]
	v_add_u32_e32 v151, v149, v141
	ds_read_b128 v[156:159], v151
	v_mfma_f32_16x16x32_bf16 v[84:87], v[168:171], v[176:179], v[84:87]
	v_mfma_f32_16x16x32_bf16 v[80:83], v[172:175], v[176:179], v[80:83]
	v_add_u32_e32 v151, v149, v142
	ds_read_b128 v[176:179], v151
	s_waitcnt lgkmcnt(3)
	v_mfma_f32_16x16x32_bf16 v[76:79], v[160:163], v[180:183], v[76:79]
	v_mfma_f32_16x16x32_bf16 v[72:75], v[164:167], v[180:183], v[72:75]
	v_mfma_f32_16x16x32_bf16 v[68:71], v[168:171], v[180:183], v[68:71]
	v_mfma_f32_16x16x32_bf16 v[64:67], v[172:175], v[180:183], v[64:67]
	v_add_u32_e32 v151, v149, v143
	ds_read_b128 v[180:183], v151
	s_waitcnt lgkmcnt(3)
	v_mfma_f32_16x16x32_bf16 v[60:63], v[160:163], v[152:155], v[60:63]
	v_mfma_f32_16x16x32_bf16 v[56:59], v[164:167], v[152:155], v[56:59]
	v_mfma_f32_16x16x32_bf16 v[52:55], v[168:171], v[152:155], v[52:55]
	v_mfma_f32_16x16x32_bf16 v[48:51], v[172:175], v[152:155], v[48:51]
	s_waitcnt lgkmcnt(2)
	v_mfma_f32_16x16x32_bf16 v[44:47], v[160:163], v[156:159], v[44:47]
	v_mfma_f32_16x16x32_bf16 v[40:43], v[164:167], v[156:159], v[40:43]
	v_mfma_f32_16x16x32_bf16 v[36:39], v[168:171], v[156:159], v[36:39]
	v_mfma_f32_16x16x32_bf16 v[32:35], v[172:175], v[156:159], v[32:35]
	s_waitcnt vmcnt(0)
	s_add_u32 s26, s26, 0x100
	s_addc_u32 s27, s27, 0
	s_add_i32 s62, s62, 2
	s_cmpk_lg_i32 s26, 0x1000
	s_waitcnt lgkmcnt(0)
	s_barrier
	s_cbranch_scc1 .LBB0_789
	v_mfma_f32_16x16x32_bf16 v[28:31], v[160:163], v[176:179], v[28:31]
	v_mfma_f32_16x16x32_bf16 v[12:15], v[160:163], v[180:183], v[12:15]
	v_mfma_f32_16x16x32_bf16 v[24:27], v[164:167], v[176:179], v[24:27]
	v_mfma_f32_16x16x32_bf16 v[4:7], v[164:167], v[180:183], v[4:7]
	v_mfma_f32_16x16x32_bf16 v[20:23], v[168:171], v[176:179], v[20:23]
	v_mfma_f32_16x16x32_bf16 v[8:11], v[168:171], v[180:183], v[8:11]
	v_mfma_f32_16x16x32_bf16 v[16:19], v[172:175], v[176:179], v[16:19]
	v_mfma_f32_16x16x32_bf16 v[0:3], v[172:175], v[180:183], v[0:3]
	s_nop 15
	s_nop 15
	v_mov_b32_e32 v128, v184
	s_movk_i32 s3, 0xff80
	v_and_b32_e32 v130, 15, v128
	v_ashrrev_i32_e32 v131, 1, v128
	v_and_or_b32 v141, v131, s3, v130
	v_lshl_add_u32 v140, v141, 2, v202
	ds_read_b32 v134, v140
	s_lshl_b32 s2, s0, 8
	v_add_u32_e32 v130, s39, v141
	v_and_b32_e32 v129, 0xc0, v128
	s_cmp_gt_i32 s0, 7
	v_lshrrev_b32_e32 v128, 2, v128
	v_ashrrev_i32_e32 v131, 31, v130
	s_cselect_b64 s[0:1], -1, 0
	v_and_b32_e32 v128, 12, v128
	v_lshlrev_b64 v[138:139], 12, v[130:131]
	v_or3_b32 v128, v129, s2, v128
	v_lshl_add_u64 v[132:133], s[20:21], 0, v[138:139]
	s_waitcnt lgkmcnt(0)
	v_pk_mul_f32 v[136:137], v[124:125], v[134:135] op_sel_hi:[1,0]
	v_pk_mul_f32 v[126:127], v[126:127], v[134:135] op_sel_hi:[1,0]
	s_mov_b64 s[2:3], -1
	s_and_b64 vcc, exec, s[0:1]
	s_cbranch_vccz .LBB0_792
	v_mov_b32_e32 v129, v147
	v_cvt_pk_bf16_f32 v124, v136, v137
	v_cvt_pk_bf16_f32 v125, v126, v127
	v_lshl_add_u64 v[142:143], v[128:129], 1, v[132:133]
	global_store_dwordx2 v[142:143], v[124:125], off offset:-4096
	s_mov_b64 s[2:3], 0
